# all global stores write-through (sc1) and buffer_wbl2 dropped from the grid barriers; cross-tile DMA prefetch in GEMMs
# speedup vs baseline: 1.4095x; 1.0672x over previous
.LBB0_13:
	v_lshl_add_u64 v[34:35], v[20:21], 0, s[8:9]
	v_add_co_u32_e64 v62, s[0:1], s3, v34
	global_load_dwordx4 v[30:33], v[34:35], off
	s_nop 0
	v_addc_co_u32_e64 v63, s[0:1], 0, v35, s[0:1]
	v_add_co_u32_e64 v64, s[0:1], s10, v34
	s_add_u32 s8, s8, 0x30000
	s_nop 0
	v_addc_co_u32_e64 v65, s[0:1], 0, v35, s[0:1]
	v_add_co_u32_e64 v66, s[0:1], s11, v34
	s_addc_u32 s9, s9, 0
	s_nop 0
	v_addc_co_u32_e64 v67, s[0:1], 0, v35, s[0:1]
	v_add_co_u32_e64 v68, s[0:1], s20, v34
	s_cmp_eq_u32 s8, 0x180000
	s_nop 0
	v_addc_co_u32_e64 v69, s[0:1], 0, v35, s[0:1]
	v_add_co_u32_e64 v70, s[0:1], s21, v34
	s_nop 1
	v_addc_co_u32_e64 v71, s[0:1], 0, v35, s[0:1]
	v_add_co_u32_e64 v72, s[0:1], s22, v34
	s_nop 1
	v_addc_co_u32_e64 v73, s[0:1], 0, v35, s[0:1]
	v_add_co_u32_e64 v74, s[0:1], s23, v34
	s_nop 1
	v_addc_co_u32_e64 v75, s[0:1], 0, v35, s[0:1]
	global_load_dwordx4 v[34:37], v[62:63], off
	global_load_dwordx4 v[38:41], v[64:65], off
	global_load_dwordx4 v[42:45], v[66:67], off
	global_load_dwordx4 v[46:49], v[68:69], off
	global_load_dwordx4 v[50:53], v[70:71], off
	global_load_dwordx4 v[54:57], v[72:73], off
	global_load_dwordx4 v[58:61], v[74:75], off
	ds_read_b128 v[62:65], v28
	ds_read_b128 v[66:69], v28 offset:16
	ds_read_b128 v[70:73], v28 offset:4096
	ds_read_b128 v[74:77], v28 offset:4112
	ds_read_b128 v[78:81], v28 offset:8192
	ds_read_b128 v[82:85], v28 offset:8208
	s_waitcnt lgkmcnt(5)
	v_mov_b32_e32 v86, v65
	s_waitcnt lgkmcnt(3)
	v_mov_b32_e32 v88, v73
	v_mov_b32_e32 v92, v69
	s_waitcnt lgkmcnt(1)
	v_mov_b32_e32 v90, v81
	v_mov_b32_e32 v94, v77
	s_waitcnt lgkmcnt(0)
	v_mov_b32_e32 v96, v85
	v_add_u32_e32 v28, 32, v28
	s_waitcnt vmcnt(7)
	v_pk_fma_f32 v[10:11], v[62:63], v[30:31], v[10:11] op_sel_hi:[0,1,1]
	v_pk_fma_f32 v[12:13], v[62:63], v[32:33], v[12:13] op_sel_hi:[0,1,1]
	v_pk_fma_f32 v[6:7], v[30:31], v[70:71], v[6:7] op_sel_hi:[1,0,1]
	v_pk_fma_f32 v[8:9], v[32:33], v[70:71], v[8:9] op_sel_hi:[1,0,1]
	v_pk_fma_f32 v[2:3], v[30:31], v[78:79], v[2:3] op_sel_hi:[1,0,1]
	v_pk_fma_f32 v[4:5], v[32:33], v[78:79], v[4:5] op_sel_hi:[1,0,1]
	s_waitcnt vmcnt(6)
	v_pk_fma_f32 v[10:11], v[62:63], v[34:35], v[10:11] op_sel:[1,0,0]
	v_pk_fma_f32 v[12:13], v[62:63], v[36:37], v[12:13] op_sel:[1,0,0]
	v_pk_fma_f32 v[6:7], v[34:35], v[70:71], v[6:7] op_sel:[0,1,0]
	v_pk_fma_f32 v[8:9], v[36:37], v[70:71], v[8:9] op_sel:[0,1,0]
	v_pk_fma_f32 v[2:3], v[34:35], v[78:79], v[2:3] op_sel:[0,1,0]
	v_pk_fma_f32 v[4:5], v[36:37], v[78:79], v[4:5] op_sel:[0,1,0]
	s_waitcnt vmcnt(5)
	v_pk_fma_f32 v[10:11], v[64:65], v[38:39], v[10:11] op_sel_hi:[0,1,1]
	v_pk_fma_f32 v[12:13], v[64:65], v[40:41], v[12:13] op_sel_hi:[0,1,1]
	v_pk_fma_f32 v[6:7], v[38:39], v[72:73], v[6:7] op_sel_hi:[1,0,1]
	v_pk_fma_f32 v[8:9], v[40:41], v[72:73], v[8:9] op_sel_hi:[1,0,1]
	v_pk_fma_f32 v[2:3], v[38:39], v[80:81], v[2:3] op_sel_hi:[1,0,1]
	v_pk_fma_f32 v[4:5], v[40:41], v[80:81], v[4:5] op_sel_hi:[1,0,1]
	s_waitcnt vmcnt(4)
	v_pk_fma_f32 v[10:11], v[86:87], v[42:43], v[10:11] op_sel_hi:[0,1,1]
	v_pk_fma_f32 v[12:13], v[86:87], v[44:45], v[12:13] op_sel_hi:[0,1,1]
	v_pk_fma_f32 v[6:7], v[42:43], v[88:89], v[6:7] op_sel_hi:[1,0,1]
	v_pk_fma_f32 v[8:9], v[44:45], v[88:89], v[8:9] op_sel_hi:[1,0,1]
	v_pk_fma_f32 v[2:3], v[42:43], v[90:91], v[2:3] op_sel_hi:[1,0,1]
	v_pk_fma_f32 v[4:5], v[44:45], v[90:91], v[4:5] op_sel_hi:[1,0,1]
	s_waitcnt vmcnt(3)
	v_pk_fma_f32 v[10:11], v[66:67], v[46:47], v[10:11] op_sel_hi:[0,1,1]
	v_pk_fma_f32 v[12:13], v[66:67], v[48:49], v[12:13] op_sel_hi:[0,1,1]
	v_pk_fma_f32 v[6:7], v[46:47], v[74:75], v[6:7] op_sel_hi:[1,0,1]
	v_pk_fma_f32 v[8:9], v[48:49], v[74:75], v[8:9] op_sel_hi:[1,0,1]
	v_pk_fma_f32 v[2:3], v[46:47], v[82:83], v[2:3] op_sel_hi:[1,0,1]
	v_pk_fma_f32 v[4:5], v[48:49], v[82:83], v[4:5] op_sel_hi:[1,0,1]
	s_waitcnt vmcnt(2)
	v_pk_fma_f32 v[10:11], v[66:67], v[50:51], v[10:11] op_sel:[1,0,0]
	v_pk_fma_f32 v[12:13], v[66:67], v[52:53], v[12:13] op_sel:[1,0,0]
	v_pk_fma_f32 v[6:7], v[50:51], v[74:75], v[6:7] op_sel:[0,1,0]
	v_pk_fma_f32 v[8:9], v[52:53], v[74:75], v[8:9] op_sel:[0,1,0]
	v_pk_fma_f32 v[2:3], v[50:51], v[82:83], v[2:3] op_sel:[0,1,0]
	v_pk_fma_f32 v[4:5], v[52:53], v[82:83], v[4:5] op_sel:[0,1,0]
	s_waitcnt vmcnt(1)
	v_pk_fma_f32 v[10:11], v[68:69], v[54:55], v[10:11] op_sel_hi:[0,1,1]
	v_pk_fma_f32 v[12:13], v[68:69], v[56:57], v[12:13] op_sel_hi:[0,1,1]
	v_pk_fma_f32 v[6:7], v[54:55], v[76:77], v[6:7] op_sel_hi:[1,0,1]
	v_pk_fma_f32 v[8:9], v[56:57], v[76:77], v[8:9] op_sel_hi:[1,0,1]
	v_pk_fma_f32 v[2:3], v[54:55], v[84:85], v[2:3] op_sel_hi:[1,0,1]
	v_pk_fma_f32 v[4:5], v[56:57], v[84:85], v[4:5] op_sel_hi:[1,0,1]
	s_waitcnt vmcnt(0)
	v_pk_fma_f32 v[10:11], v[92:93], v[58:59], v[10:11] op_sel_hi:[0,1,1]
	v_pk_fma_f32 v[12:13], v[92:93], v[60:61], v[12:13] op_sel_hi:[0,1,1]
	v_pk_fma_f32 v[6:7], v[58:59], v[94:95], v[6:7] op_sel_hi:[1,0,1]
	v_pk_fma_f32 v[8:9], v[60:61], v[94:95], v[8:9] op_sel_hi:[1,0,1]
	v_pk_fma_f32 v[2:3], v[58:59], v[96:97], v[2:3] op_sel_hi:[1,0,1]
	v_pk_fma_f32 v[4:5], v[60:61], v[96:97], v[4:5] op_sel_hi:[1,0,1]
	s_cbranch_scc0 .LBB0_13
	ds_write_b128 v24, v[10:13] offset:12288
	ds_write_b128 v24, v[6:9] offset:12544
	ds_write_b128 v24, v[2:5] offset:12800
	s_waitcnt lgkmcnt(0)
	s_barrier
	s_and_saveexec_b64 s[0:1], vcc
	s_cbranch_execz .LBB0_11
	v_mov_b32_e32 v2, s24
	ds_read_b64 v[2:3], v2
	s_mul_i32 s7, s27, 0x1800
	s_add_i32 s7, s7, s6
	v_or_b32_e32 v4, s7, v25
	v_ashrrev_i32_e32 v5, 31, v4
	s_waitcnt lgkmcnt(0)
	v_readfirstlane_b32 s8, v2
	v_readfirstlane_b32 s9, v3
	s_nop 0
	v_mov_b32_e32 v2, s8
	v_mov_b32_e32 v3, s9
	v_lshl_add_u64 v[2:3], v[4:5], 2, v[2:3]
	global_load_dword v32, v[2:3], off
	ds_read2st64_b32 v[2:3], v27 offset0:48 offset1:51
	ds_read2st64_b32 v[4:5], v27 offset0:54 offset1:57
	ds_read2st64_b32 v[6:7], v27 offset0:60 offset1:63
	ds_read2st64_b32 v[8:9], v27 offset0:66 offset1:69
	ds_read2st64_b32 v[10:11], v27 offset0:72 offset1:75
	ds_read2st64_b32 v[12:13], v27 offset0:78 offset1:81
	ds_read2st64_b32 v[20:21], v27 offset0:84 offset1:87
	ds_read2st64_b32 v[28:29], v27 offset0:90 offset1:93
	s_waitcnt lgkmcnt(7)
	v_add_f32_e32 v2, 0, v2
	v_add_f32_e32 v2, v2, v3
	s_waitcnt lgkmcnt(6)
	v_add_f32_e32 v2, v2, v4
	v_add_f32_e32 v2, v2, v5
	s_waitcnt lgkmcnt(5)
	v_add_f32_e32 v2, v2, v6
	v_add_f32_e32 v2, v2, v7
	s_waitcnt lgkmcnt(4)
	v_add_f32_e32 v2, v2, v8
	v_add_f32_e32 v2, v2, v9
	s_waitcnt lgkmcnt(3)
	v_add_f32_e32 v2, v2, v10
	v_add_f32_e32 v2, v2, v11
	s_waitcnt lgkmcnt(2)
	v_add_f32_e32 v2, v2, v12
	v_mad_u64_u32 v[30:31], s[8:9], s27, 3, v[16:17]
	v_add_f32_e32 v2, v2, v13
	v_mul_lo_u32 v30, v30, s25
	s_waitcnt lgkmcnt(1)
	v_add_f32_e32 v2, v2, v20
	v_add_u32_e32 v30, s6, v30
	v_add_f32_e32 v2, v2, v21
	v_or_b32_e32 v30, v30, v25
	s_waitcnt lgkmcnt(0)
	v_add_f32_e32 v2, v2, v28
	v_ashrrev_i32_e32 v31, 31, v30
	v_add_f32_e32 v2, v2, v29
	s_waitcnt vmcnt(0)
	v_add_f32_e32 v4, v2, v32
	v_lshl_add_u64 v[2:3], v[30:31], 2, s[4:5]
	global_store_dword v[2:3], v4, off sc1
	s_branch .LBB0_11

.LBB0_18:
	v_lshrrev_b32_e32 v7, 8, v6
	v_mad_i32_i24 v8, v7, s3, v3
	v_add_u32_e32 v6, s20, v6
	v_ashrrev_i32_e32 v9, 31, v8
	v_cmp_lt_i32_e32 vcc, s8, v6
	v_lshl_add_u64 v[8:9], v[8:9], 2, s[4:5]
	s_or_b64 s[6:7], vcc, s[6:7]
	global_store_dword v[8:9], v4, off sc1
	v_add_co_u32_e32 v8, vcc, 0x10000, v8
	s_nop 1
	v_addc_co_u32_e32 v9, vcc, 0, v9, vcc
	global_store_dword v[8:9], v5, off offset:2048 sc1
	s_andn2_b64 exec, exec, s[6:7]
	s_cbranch_execnz .LBB0_18

.LBB0_21:
	s_or_b64 exec, exec, s[0:1]
	v_mul_f32_e32 v19, v6, v6
	v_fmamk_f32 v20, v19, 0xb94c1982, v9
	v_fmaak_f32 v20, v19, v20, 0xbe2aaa9d
	v_mul_f32_e32 v20, v19, v20
	v_fmac_f32_e32 v6, v6, v20
	v_fmamk_f32 v20, v19, 0x37d75334, v10
	v_fmaak_f32 v20, v19, v20, 0x3d2aabf7
	v_fmaak_f32 v20, v19, v20, 0xbf000004
	v_fma_f32 v19, v19, v20, 1.0
	v_lshlrev_b32_e32 v20, 30, v18
	v_and_b32_e32 v18, 1, v18
	v_cmp_eq_u32_e64 s[0:1], 0, v18
	v_xor_b32_e32 v16, v16, v15
	v_and_b32_e32 v21, 0x80000000, v20
	v_cndmask_b32_e64 v18, v19, v6, s[0:1]
	v_xor_b32_e32 v6, 0x80000000, v6
	v_xor_b32_e32 v16, v16, v18
	v_cndmask_b32_e64 v6, v6, v19, s[0:1]
	v_xor_b32_e32 v16, v16, v21
	v_bitop3_b32 v6, v6, v20, s39 bitop3:0x78
	v_cmp_class_f32_e64 s[0:1], v15, s40
	v_add_u32_e32 v14, s20, v14
	s_nop 0
	v_cndmask_b32_e64 v18, v13, v6, s[0:1]
	v_cndmask_b32_e64 v19, v13, v16, s[0:1]
	v_cmp_lt_i32_e64 s[0:1], s41, v14
	global_store_dwordx2 v[4:5], v[18:19], off sc1
	s_or_b64 s[26:27], s[0:1], s[26:27]
	v_lshl_add_u64 v[4:5], v[4:5], 0, s[24:25]
	s_andn2_b64 exec, exec, s[26:27]
	s_cbranch_execz .LBB0_26

.LBB0_28:
	s_or_b64 exec, exec, s[0:1]
	v_mul_f32_e32 v18, v6, v6
	v_fmamk_f32 v19, v18, 0xb94c1982, v3
	v_fmaak_f32 v19, v18, v19, 0xbe2aaa9d
	v_mul_f32_e32 v19, v18, v19
	v_fmac_f32_e32 v6, v6, v19
	v_fmamk_f32 v19, v18, 0x37d75334, v9
	v_fmaak_f32 v19, v18, v19, 0x3d2aabf7
	v_fmaak_f32 v19, v18, v19, 0xbf000004
	v_fma_f32 v18, v18, v19, 1.0
	v_lshlrev_b32_e32 v19, 30, v16
	v_and_b32_e32 v16, 1, v16
	v_cmp_eq_u32_e64 s[0:1], 0, v16
	v_xor_b32_e32 v15, v15, v14
	v_and_b32_e32 v20, 0x80000000, v19
	v_cndmask_b32_e64 v16, v18, v6, s[0:1]
	v_xor_b32_e32 v6, 0x80000000, v6
	v_xor_b32_e32 v15, v15, v16
	v_cndmask_b32_e64 v6, v6, v18, s[0:1]
	v_xor_b32_e32 v15, v15, v20
	v_bitop3_b32 v6, v6, v19, s39 bitop3:0x78
	v_cmp_class_f32_e64 s[0:1], v14, s40
	v_add_u32_e32 v13, s20, v13
	s_nop 0
	v_cndmask_b32_e64 v14, v12, v6, s[0:1]
	v_cndmask_b32_e64 v15, v12, v15, s[0:1]
	v_cmp_lt_i32_e64 s[0:1], s41, v13
	global_store_dwordx2 v[4:5], v[14:15], off sc1
	s_or_b64 s[26:27], s[0:1], s[26:27]
	v_lshl_add_u64 v[4:5], v[4:5], 0, s[24:25]
	s_andn2_b64 exec, exec, s[26:27]
	s_cbranch_execz .LBB0_33

.LBB0_36:
	v_ashrrev_i32_e32 v13, 31, v4
	v_mov_b32_e32 v12, v4
	v_ashrrev_i32_e32 v11, 31, v5
	v_mov_b32_e32 v10, v5
	v_lshl_add_u64 v[12:13], v[12:13], 2, s[8:9]
	v_lshl_add_u64 v[10:11], v[10:11], 2, s[8:9]
	global_load_dword v3, v[12:13], off
	global_load_dword v9, v[10:11], off
	v_mul_i32_i24_sdwa v10, sext(v4), s11 dst_sel:DWORD dst_unused:UNUSED_PAD src0_sel:WORD_1 src1_sel:DWORD
	v_mul_i32_i24_sdwa v11, sext(v5), s11 dst_sel:DWORD dst_unused:UNUSED_PAD src0_sel:WORD_1 src1_sel:DWORD
	v_or_b32_sdwa v10, v10, v4 dst_sel:DWORD dst_unused:UNUSED_PAD src0_sel:DWORD src1_sel:WORD_0
	v_add_u32_e32 v8, -2, v8
	v_or_b32_sdwa v11, v11, v5 dst_sel:DWORD dst_unused:UNUSED_PAD src0_sel:DWORD src1_sel:WORD_0
	v_add_u32_e32 v10, 0x200000, v10
	v_cmp_eq_u32_e32 vcc, 0, v8
	v_add_u32_e32 v12, 0x200000, v11
	v_ashrrev_i32_e32 v11, 31, v10
	v_add_u32_e32 v5, s10, v5
	v_add_u32_e32 v4, s3, v4
	s_or_b64 s[22:23], vcc, s[22:23]
	v_ashrrev_i32_e32 v13, 31, v12
	v_lshl_add_u64 v[10:11], v[10:11], 1, s[6:7]
	v_lshl_add_u64 v[12:13], v[12:13], 1, s[6:7]
	s_waitcnt vmcnt(0)
	v_cvt_pk_bf16_f32 v3, v3, v9
	global_store_short v[10:11], v3, off sc1
	global_store_short_d16_hi v[12:13], v3, off sc1
	s_andn2_b64 exec, exec, s[22:23]
	s_cbranch_execnz .LBB0_36
	s_or_b64 exec, exec, s[22:23]
	v_cmp_ne_u32_e32 vcc, v6, v7
	v_mad_u64_u32 v[2:3], s[10:11], v7, s20, v[2:3]
	s_orn2_b64 s[22:23], vcc, exec

.LBB0_40:
	global_load_dword v3, v[4:5], off
	v_mul_i32_i24_sdwa v6, sext(v2), s3 dst_sel:DWORD dst_unused:UNUSED_PAD src0_sel:WORD_1 src1_sel:DWORD
	v_and_or_b32 v6, v2, s10, v6
	v_add_u32_e32 v2, s20, v2
	v_add_u32_e32 v6, 0x200000, v6
	v_cmp_lt_i32_e32 vcc, s11, v2
	v_ashrrev_i32_e32 v7, 31, v6
	v_lshl_add_u64 v[4:5], v[4:5], 0, s[0:1]
	s_or_b64 s[8:9], vcc, s[8:9]
	v_lshl_add_u64 v[6:7], v[6:7], 1, s[6:7]
	s_waitcnt vmcnt(0)
	v_cvt_pk_bf16_f32 v3, v3, s0
	global_store_short v[6:7], v3, off sc1
	s_andn2_b64 exec, exec, s[8:9]
	s_cbranch_execnz .LBB0_40

.LBB0_43:
	s_or_b64 exec, exec, s[0:1]
	s_waitcnt vmcnt(0)
	ds_write2_b32 v23, v2, v3 offset1:1
	ds_write2_b32 v24, v4, v5 offset1:1
	s_waitcnt lgkmcnt(0)
	s_barrier
	ds_read2_b32 v[6:7], v14 offset1:32
	ds_read2_b32 v[26:27], v14 offset0:65 offset1:97
	ds_read2_b32 v[28:29], v14 offset0:130 offset1:162
	ds_read2_b32 v[30:31], v14 offset0:195 offset1:227
	ds_read2_b32 v[32:33], v25 offset0:4 offset1:36
	ds_read2_b32 v[34:35], v25 offset0:69 offset1:101
	ds_read2_b32 v[36:37], v25 offset0:134 offset1:166
	ds_read2_b32 v[38:39], v25 offset0:199 offset1:231
	s_lshl_b32 s0, s23, 10
	s_sub_i32 s0, s20, s0
	v_add_u32_e32 v42, s22, v13
	s_ashr_i32 s1, s0, 31
	v_ashrrev_i32_e32 v43, 31, v42
	v_lshl_add_u64 v[40:41], s[0:1], 1, v[10:11]
	v_lshlrev_b64 v[44:45], 11, v[42:43]
	s_waitcnt lgkmcnt(6)
	v_cvt_pk_bf16_f32 v2, v6, v26
	s_waitcnt lgkmcnt(4)
	v_cvt_pk_bf16_f32 v3, v28, v30
	s_waitcnt lgkmcnt(2)
	v_cvt_pk_bf16_f32 v4, v32, v34
	s_waitcnt lgkmcnt(0)
	v_cvt_pk_bf16_f32 v5, v36, v38
	v_lshl_add_u64 v[44:45], v[40:41], 0, v[44:45]
	v_add_u32_e32 v6, 32, v42
	global_store_dwordx4 v[44:45], v[2:5], off sc1
	s_add_i32 s9, s9, s33
	s_add_i32 s20, s20, s21
	v_cvt_pk_bf16_f32 v2, v7, v27
	v_ashrrev_i32_e32 v7, 31, v6
	v_lshlrev_b64 v[6:7], 11, v[6:7]
	v_cvt_pk_bf16_f32 v3, v29, v31
	v_cvt_pk_bf16_f32 v4, v33, v35
	v_cvt_pk_bf16_f32 v5, v37, v39
	v_lshl_add_u64 v[6:7], v[40:41], 0, v[6:7]
	s_cmpk_lt_i32 s9, 0xc0
	v_add_u32_e32 v15, s11, v15
	global_store_dwordx4 v[6:7], v[2:5], off sc1
	s_barrier
	s_cbranch_scc0 .LBB0_52

.LBB0_54:
	s_or_b64 exec, exec, s[0:1]
	s_waitcnt vmcnt(0)
	ds_write2_b32 v24, v2, v3 offset1:1
	ds_write2_b32 v25, v4, v5 offset1:1
	s_waitcnt lgkmcnt(0)
	s_barrier
	ds_read2_b32 v[6:7], v14 offset1:32
	ds_read2_b32 v[28:29], v14 offset0:65 offset1:97
	ds_read2_b32 v[30:31], v14 offset0:130 offset1:162
	ds_read2_b32 v[32:33], v14 offset0:195 offset1:227
	ds_read2_b32 v[34:35], v26 offset0:4 offset1:36
	ds_read2_b32 v[36:37], v26 offset0:69 offset1:101
	ds_read2_b32 v[38:39], v26 offset0:134 offset1:166
	ds_read2_b32 v[40:41], v26 offset0:199 offset1:231
	s_mulk_i32 s24, 0xfe80
	s_add_i32 s0, s11, s24
	s_ashr_i32 s1, s0, 31
	v_lshl_add_u64 v[42:43], s[0:1], 1, v[10:11]
	s_waitcnt lgkmcnt(6)
	v_cvt_pk_bf16_f32 v2, v6, v28
	v_add_u32_e32 v6, s23, v13
	s_waitcnt lgkmcnt(4)
	v_cvt_pk_bf16_f32 v3, v30, v32
	s_waitcnt lgkmcnt(2)
	v_cvt_pk_bf16_f32 v4, v34, v36
	s_waitcnt lgkmcnt(0)
	v_cvt_pk_bf16_f32 v5, v38, v40
	v_mad_i64_i32 v[44:45], s[0:1], v6, s22, v[42:43]
	v_add_u32_e32 v6, 32, v6
	s_add_i32 s10, s10, s33
	s_add_i32 s11, s11, s20
	global_store_dwordx4 v[44:45], v[2:5], off sc1
	s_cmpk_lt_i32 s10, 0x90
	v_add_u32_e32 v15, s9, v15
	v_cvt_pk_bf16_f32 v2, v7, v29
	v_cvt_pk_bf16_f32 v3, v31, v33
	v_cvt_pk_bf16_f32 v4, v35, v37
	v_cvt_pk_bf16_f32 v5, v39, v41
	v_mad_i64_i32 v[6:7], s[0:1], v6, s22, v[42:43]
	global_store_dwordx4 v[6:7], v[2:5], off sc1
	s_barrier
	s_cbranch_scc0 .LBB0_63

.LBB0_65:
	s_or_b64 exec, exec, s[4:5]
	s_waitcnt vmcnt(0)
	ds_write2_b32 v25, v2, v3 offset1:1
	ds_write2_b32 v26, v4, v5 offset1:1
	s_waitcnt lgkmcnt(0)
	s_barrier
	ds_read2_b32 v[6:7], v16 offset1:32
	ds_read2_b32 v[12:13], v16 offset0:65 offset1:97
	ds_read2_b32 v[28:29], v16 offset0:130 offset1:162
	ds_read2_b32 v[30:31], v16 offset0:195 offset1:227
	ds_read2_b32 v[32:33], v27 offset0:4 offset1:36
	ds_read2_b32 v[34:35], v27 offset0:69 offset1:101
	ds_read2_b32 v[36:37], v27 offset0:134 offset1:166
	ds_read2_b32 v[38:39], v27 offset0:199 offset1:231
	s_lshl_b32 s4, s20, 8
	s_sub_i32 s4, s10, s4
	v_lshl_add_u32 v42, s20, 6, v15
	s_ashr_i32 s5, s4, 31
	v_ashrrev_i32_e32 v43, 31, v42
	v_lshl_add_u64 v[40:41], s[4:5], 1, v[10:11]
	v_lshlrev_b64 v[44:45], 9, v[42:43]
	s_waitcnt lgkmcnt(6)
	v_cvt_pk_bf16_f32 v2, v6, v12
	s_waitcnt lgkmcnt(4)
	v_cvt_pk_bf16_f32 v3, v28, v30
	s_waitcnt lgkmcnt(2)
	v_cvt_pk_bf16_f32 v4, v32, v34
	s_waitcnt lgkmcnt(0)
	v_cvt_pk_bf16_f32 v5, v36, v38
	v_lshl_add_u64 v[44:45], v[40:41], 0, v[44:45]
	v_add_u32_e32 v6, 32, v42
	global_store_dwordx4 v[44:45], v[2:5], off sc1
	s_add_i32 s6, s6, s33
	s_add_i32 s10, s10, s11
	v_cvt_pk_bf16_f32 v2, v7, v13
	v_ashrrev_i32_e32 v7, 31, v6
	v_lshlrev_b64 v[6:7], 9, v[6:7]
	v_cvt_pk_bf16_f32 v3, v29, v31
	v_cvt_pk_bf16_f32 v4, v33, v35
	v_cvt_pk_bf16_f32 v5, v37, v39
	v_lshl_add_u64 v[6:7], v[40:41], 0, v[6:7]
	s_cmpk_lt_i32 s6, 0x80
	v_add_u32_e32 v18, s7, v18
	global_store_dwordx4 v[6:7], v[2:5], off sc1
	s_barrier
	s_cbranch_scc0 .LBB0_74

.LBB0_76:
	s_or_b64 exec, exec, s[4:5]
	s_waitcnt vmcnt(0)
	ds_write2_b32 v26, v2, v3 offset1:1
	ds_write2_b32 v27, v4, v5 offset1:1
	s_waitcnt lgkmcnt(0)
	s_barrier
	ds_read2_b32 v[6:7], v18 offset1:32
	ds_read2_b32 v[12:13], v18 offset0:65 offset1:97
	ds_read2_b32 v[30:31], v18 offset0:130 offset1:162
	ds_read2_b32 v[32:33], v18 offset0:195 offset1:227
	ds_read2_b32 v[34:35], v28 offset0:4 offset1:36
	ds_read2_b32 v[36:37], v28 offset0:69 offset1:101
	ds_read2_b32 v[38:39], v28 offset0:134 offset1:166
	ds_read2_b32 v[40:41], v28 offset0:199 offset1:231
	s_lshl_b32 s4, s20, 10
	s_sub_i32 s4, s10, s4
	v_lshl_add_u32 v44, s20, 6, v15
	s_ashr_i32 s5, s4, 31
	v_ashrrev_i32_e32 v45, 31, v44
	v_lshl_add_u64 v[42:43], s[4:5], 1, v[10:11]
	v_lshlrev_b64 v[46:47], 11, v[44:45]
	s_waitcnt lgkmcnt(6)
	v_cvt_pk_bf16_f32 v2, v6, v12
	s_waitcnt lgkmcnt(4)
	v_cvt_pk_bf16_f32 v3, v30, v32
	s_waitcnt lgkmcnt(2)
	v_cvt_pk_bf16_f32 v4, v34, v36
	s_waitcnt lgkmcnt(0)
	v_cvt_pk_bf16_f32 v5, v38, v40
	v_lshl_add_u64 v[46:47], v[42:43], 0, v[46:47]
	v_add_u32_e32 v6, 32, v44
	global_store_dwordx4 v[46:47], v[2:5], off sc1
	s_add_i32 s6, s6, s33
	s_add_i32 s10, s10, s11
	v_cvt_pk_bf16_f32 v2, v7, v13
	v_ashrrev_i32_e32 v7, 31, v6
	v_lshlrev_b64 v[6:7], 11, v[6:7]
	v_cvt_pk_bf16_f32 v3, v31, v33
	v_cvt_pk_bf16_f32 v4, v35, v37
	v_cvt_pk_bf16_f32 v5, v39, v41
	v_lshl_add_u64 v[6:7], v[42:43], 0, v[6:7]
	s_cmpk_lt_i32 s6, 0x100
	v_add_u32_e32 v19, s7, v19
	global_store_dwordx4 v[6:7], v[2:5], off sc1
	s_barrier
	s_cbranch_scc0 .LBB0_85

.LBB0_87:
	s_or_b64 exec, exec, s[4:5]
	s_waitcnt vmcnt(0)
	ds_write2_b32 v26, v2, v3 offset1:1
	ds_write2_b32 v27, v4, v5 offset1:1
	s_waitcnt lgkmcnt(0)
	s_barrier
	ds_read2_b32 v[6:7], v18 offset1:32
	ds_read2_b32 v[12:13], v18 offset0:65 offset1:97
	ds_read2_b32 v[30:31], v18 offset0:130 offset1:162
	ds_read2_b32 v[32:33], v18 offset0:195 offset1:227
	ds_read2_b32 v[34:35], v28 offset0:4 offset1:36
	ds_read2_b32 v[36:37], v28 offset0:69 offset1:101
	ds_read2_b32 v[38:39], v28 offset0:134 offset1:166
	ds_read2_b32 v[40:41], v28 offset0:199 offset1:231
	s_lshl_b32 s4, s20, 10
	s_sub_i32 s4, s10, s4
	v_lshl_add_u32 v44, s20, 6, v15
	s_ashr_i32 s5, s4, 31
	v_ashrrev_i32_e32 v45, 31, v44
	v_lshl_add_u64 v[42:43], s[4:5], 1, v[10:11]
	v_lshlrev_b64 v[46:47], 11, v[44:45]
	s_waitcnt lgkmcnt(6)
	v_cvt_pk_bf16_f32 v2, v6, v12
	s_waitcnt lgkmcnt(4)
	v_cvt_pk_bf16_f32 v3, v30, v32
	s_waitcnt lgkmcnt(2)
	v_cvt_pk_bf16_f32 v4, v34, v36
	s_waitcnt lgkmcnt(0)
	v_cvt_pk_bf16_f32 v5, v38, v40
	v_lshl_add_u64 v[46:47], v[42:43], 0, v[46:47]
	v_add_u32_e32 v6, 32, v44
	global_store_dwordx4 v[46:47], v[2:5], off sc1
	s_add_i32 s6, s6, s33
	s_add_i32 s10, s10, s11
	v_cvt_pk_bf16_f32 v2, v7, v13
	v_ashrrev_i32_e32 v7, 31, v6
	v_lshlrev_b64 v[6:7], 11, v[6:7]
	v_cvt_pk_bf16_f32 v3, v31, v33
	v_cvt_pk_bf16_f32 v4, v35, v37
	v_cvt_pk_bf16_f32 v5, v39, v41
	v_lshl_add_u64 v[6:7], v[42:43], 0, v[6:7]
	s_cmpk_lt_i32 s6, 0x300
	v_add_u32_e32 v19, s7, v19
	global_store_dwordx4 v[6:7], v[2:5], off sc1
	s_barrier
	s_cbranch_scc0 .LBB0_96

.LBB0_109:
	s_or_b64 exec, exec, s[4:5]
	s_waitcnt vmcnt(0)
	ds_write2_b32 v26, v2, v3 offset1:1
	ds_write2_b32 v27, v4, v5 offset1:1
	s_waitcnt lgkmcnt(0)
	s_barrier
	ds_read2_b32 v[6:7], v18 offset1:32
	ds_read2_b32 v[12:13], v18 offset0:65 offset1:97
	ds_read2_b32 v[30:31], v18 offset0:130 offset1:162
	ds_read2_b32 v[32:33], v18 offset0:195 offset1:227
	ds_read2_b32 v[34:35], v28 offset0:4 offset1:36
	ds_read2_b32 v[36:37], v28 offset0:69 offset1:101
	ds_read2_b32 v[38:39], v28 offset0:134 offset1:166
	ds_read2_b32 v[40:41], v28 offset0:199 offset1:231
	s_lshl_b32 s4, s11, 10
	s_sub_i32 s4, s7, s4
	v_lshl_add_u32 v44, s11, 6, v15
	s_ashr_i32 s5, s4, 31
	v_ashrrev_i32_e32 v45, 31, v44
	v_lshl_add_u64 v[42:43], s[4:5], 1, v[10:11]
	v_lshlrev_b64 v[46:47], 11, v[44:45]
	s_waitcnt lgkmcnt(6)
	v_cvt_pk_bf16_f32 v2, v6, v12
	s_waitcnt lgkmcnt(4)
	v_cvt_pk_bf16_f32 v3, v30, v32
	s_waitcnt lgkmcnt(2)
	v_cvt_pk_bf16_f32 v4, v34, v36
	s_waitcnt lgkmcnt(0)
	v_cvt_pk_bf16_f32 v5, v38, v40
	v_lshl_add_u64 v[46:47], v[42:43], 0, v[46:47]
	v_add_u32_e32 v6, 32, v44
	global_store_dwordx4 v[46:47], v[2:5], off sc1
	s_add_i32 s6, s6, s33
	s_add_i32 s7, s7, s10
	v_cvt_pk_bf16_f32 v2, v7, v13
	v_ashrrev_i32_e32 v7, 31, v6
	v_lshlrev_b64 v[6:7], 11, v[6:7]
	v_cvt_pk_bf16_f32 v3, v31, v33
	v_cvt_pk_bf16_f32 v4, v35, v37
	v_cvt_pk_bf16_f32 v5, v39, v41
	v_lshl_add_u64 v[6:7], v[42:43], 0, v[6:7]
	s_cmpk_lt_i32 s6, 0x180
	v_add_u32_e32 v19, s9, v19
	global_store_dwordx4 v[6:7], v[2:5], off sc1
	s_barrier
	s_cbranch_scc0 .LBB0_118

.LBB0_120:
	s_or_b64 exec, exec, s[4:5]
	s_waitcnt vmcnt(0)
	ds_write2_b32 v26, v2, v3 offset1:1
	ds_write2_b32 v27, v4, v5 offset1:1
	s_waitcnt lgkmcnt(0)
	s_barrier
	ds_read2_b32 v[6:7], v18 offset1:32
	ds_read2_b32 v[12:13], v18 offset0:65 offset1:97
	ds_read2_b32 v[30:31], v18 offset0:130 offset1:162
	ds_read2_b32 v[32:33], v18 offset0:195 offset1:227
	ds_read2_b32 v[34:35], v28 offset0:4 offset1:36
	ds_read2_b32 v[36:37], v28 offset0:69 offset1:101
	ds_read2_b32 v[38:39], v28 offset0:134 offset1:166
	ds_read2_b32 v[40:41], v28 offset0:199 offset1:231
	s_lshl_b32 s4, s11, 10
	s_sub_i32 s4, s9, s4
	v_lshl_add_u32 v44, s11, 6, v15
	s_ashr_i32 s5, s4, 31
	v_ashrrev_i32_e32 v45, 31, v44
	v_lshl_add_u64 v[42:43], s[4:5], 1, v[10:11]
	v_lshlrev_b64 v[46:47], 11, v[44:45]
	s_waitcnt lgkmcnt(6)
	v_cvt_pk_bf16_f32 v2, v6, v12
	s_waitcnt lgkmcnt(4)
	v_cvt_pk_bf16_f32 v3, v30, v32
	s_waitcnt lgkmcnt(2)
	v_cvt_pk_bf16_f32 v4, v34, v36
	s_waitcnt lgkmcnt(0)
	v_cvt_pk_bf16_f32 v5, v38, v40
	v_lshl_add_u64 v[46:47], v[42:43], 0, v[46:47]
	v_add_u32_e32 v6, 32, v44
	global_store_dwordx4 v[46:47], v[2:5], off sc1
	s_add_i32 s6, s6, s33
	s_add_i32 s9, s9, s10
	v_cvt_pk_bf16_f32 v2, v7, v13
	v_ashrrev_i32_e32 v7, 31, v6
	v_lshlrev_b64 v[6:7], 11, v[6:7]
	v_cvt_pk_bf16_f32 v3, v31, v33
	v_cvt_pk_bf16_f32 v4, v35, v37
	v_cvt_pk_bf16_f32 v5, v39, v41
	v_lshl_add_u64 v[6:7], v[42:43], 0, v[6:7]
	s_cmpk_lt_i32 s6, 0x100
	v_add_u32_e32 v19, s7, v19
	global_store_dwordx4 v[6:7], v[2:5], off sc1
	s_barrier
	s_cbranch_scc0 .LBB0_129

.LBB0_131:
	s_or_b64 exec, exec, s[4:5]
	s_waitcnt vmcnt(0)
	ds_write2_b32 v25, v2, v3 offset1:1
	ds_write2_b32 v26, v4, v5 offset1:1
	s_waitcnt lgkmcnt(0)
	s_barrier
	ds_read2_b32 v[6:7], v18 offset1:32
	ds_read2_b32 v[12:13], v18 offset0:65 offset1:97
	ds_read2_b32 v[28:29], v18 offset0:130 offset1:162
	ds_read2_b32 v[30:31], v18 offset0:195 offset1:227
	ds_read2_b32 v[32:33], v27 offset0:4 offset1:36
	ds_read2_b32 v[34:35], v27 offset0:69 offset1:101
	ds_read2_b32 v[36:37], v27 offset0:134 offset1:166
	ds_read2_b32 v[38:39], v27 offset0:199 offset1:231
	s_lshl_b32 s4, s11, 10
	s_sub_i32 s4, s9, s4
	v_lshl_add_u32 v42, s11, 6, v15
	s_ashr_i32 s5, s4, 31
	v_ashrrev_i32_e32 v43, 31, v42
	v_lshl_add_u64 v[40:41], s[4:5], 1, v[10:11]
	v_lshlrev_b64 v[44:45], 11, v[42:43]
	s_waitcnt lgkmcnt(6)
	v_cvt_pk_bf16_f32 v2, v6, v12
	s_waitcnt lgkmcnt(4)
	v_cvt_pk_bf16_f32 v3, v28, v30
	s_waitcnt lgkmcnt(2)
	v_cvt_pk_bf16_f32 v4, v32, v34
	s_waitcnt lgkmcnt(0)
	v_cvt_pk_bf16_f32 v5, v36, v38
	v_lshl_add_u64 v[44:45], v[40:41], 0, v[44:45]
	v_add_u32_e32 v6, 32, v42
	global_store_dwordx4 v[44:45], v[2:5], off sc1
	s_add_i32 s6, s6, s33
	s_add_i32 s9, s9, s10
	v_cvt_pk_bf16_f32 v2, v7, v13
	v_ashrrev_i32_e32 v7, 31, v6
	v_lshlrev_b64 v[6:7], 11, v[6:7]
	v_cvt_pk_bf16_f32 v3, v29, v31
	v_cvt_pk_bf16_f32 v4, v33, v35
	v_cvt_pk_bf16_f32 v5, v37, v39
	v_lshl_add_u64 v[6:7], v[40:41], 0, v[6:7]
	s_cmpk_lt_i32 s6, 0x200
	v_add_u32_e32 v14, s7, v14
	global_store_dwordx4 v[6:7], v[2:5], off sc1
	s_barrier
	s_cbranch_scc0 .LBB0_140

.LBB0_142:
	s_or_b64 exec, exec, s[4:5]
	s_waitcnt vmcnt(0)
	ds_write2_b32 v23, v2, v3 offset1:1
	ds_write2_b32 v24, v4, v5 offset1:1
	s_waitcnt lgkmcnt(0)
	s_barrier
	ds_read2_b32 v[6:7], v14 offset1:32
	ds_read2_b32 v[26:27], v14 offset0:65 offset1:97
	ds_read2_b32 v[28:29], v14 offset0:130 offset1:162
	ds_read2_b32 v[30:31], v14 offset0:195 offset1:227
	ds_read2_b32 v[32:33], v25 offset0:4 offset1:36
	ds_read2_b32 v[34:35], v25 offset0:69 offset1:101
	ds_read2_b32 v[36:37], v25 offset0:134 offset1:166
	ds_read2_b32 v[38:39], v25 offset0:199 offset1:231
	s_sub_i32 s4, s7, s11
	v_add_u32_e32 v42, s10, v13
	s_ashr_i32 s5, s4, 31
	v_ashrrev_i32_e32 v43, 31, v42
	v_lshl_add_u64 v[40:41], s[4:5], 1, v[10:11]
	v_lshlrev_b64 v[44:45], 8, v[42:43]
	s_waitcnt lgkmcnt(6)
	v_cvt_pk_bf16_f32 v2, v6, v26
	s_waitcnt lgkmcnt(4)
	v_cvt_pk_bf16_f32 v3, v28, v30
	s_waitcnt lgkmcnt(2)
	v_cvt_pk_bf16_f32 v4, v32, v34
	s_waitcnt lgkmcnt(0)
	v_cvt_pk_bf16_f32 v5, v36, v38
	v_lshl_add_u64 v[44:45], v[40:41], 0, v[44:45]
	v_add_u32_e32 v6, 32, v42
	global_store_dwordx4 v[44:45], v[2:5], off sc1
	s_add_i32 s6, s6, s33
	s_add_i32 s7, s7, s9
	v_cvt_pk_bf16_f32 v2, v7, v27
	v_ashrrev_i32_e32 v7, 31, v6
	v_lshlrev_b64 v[6:7], 8, v[6:7]
	v_cvt_pk_bf16_f32 v3, v29, v31
	v_cvt_pk_bf16_f32 v4, v33, v35
	v_cvt_pk_bf16_f32 v5, v37, v39
	v_lshl_add_u64 v[6:7], v[40:41], 0, v[6:7]
	s_cmpk_lt_i32 s6, 0x80
	global_store_dwordx4 v[6:7], v[2:5], off sc1
	s_barrier
	s_cbranch_scc0 .LBB0_151

.LBB0_155:
	s_or_b64 exec, exec, s[4:5]
	v_add_u32_e32 v6, 0x30c0, v23
	s_waitcnt vmcnt(0)
	ds_write2_b32 v6, v2, v3 offset1:1
	v_add_u32_e32 v2, 0x30c8, v23
	ds_write2_b32 v2, v4, v5 offset1:1
	v_add_u32_e32 v2, 0x400, v20
	s_waitcnt lgkmcnt(0)
	s_barrier
	ds_read2_b32 v[6:7], v20 offset1:32
	ds_read2_b32 v[14:15], v20 offset0:65 offset1:97
	ds_read2_b32 v[30:31], v20 offset0:130 offset1:162
	ds_read2_b32 v[32:33], v20 offset0:195 offset1:227
	ds_read2_b32 v[34:35], v2 offset0:4 offset1:36
	ds_read2_b32 v[36:37], v2 offset0:69 offset1:101
	ds_read2_b32 v[38:39], v2 offset0:134 offset1:166
	ds_read2_b32 v[40:41], v2 offset0:199 offset1:231
	s_lshl_b32 s4, s11, 10
	s_lshl_b32 s11, s11, 6
	s_sub_i32 s4, s10, s4
	v_add_u32_e32 v44, s11, v18
	s_ashr_i32 s5, s4, 31
	v_ashrrev_i32_e32 v45, 31, v44
	v_lshl_add_u64 v[42:43], s[4:5], 1, v[12:13]
	v_lshlrev_b64 v[44:45], 11, v[44:45]
	s_waitcnt lgkmcnt(6)
	v_cvt_pk_bf16_f32 v2, v6, v14
	s_waitcnt lgkmcnt(4)
	v_cvt_pk_bf16_f32 v3, v30, v32
	s_waitcnt lgkmcnt(2)
	v_cvt_pk_bf16_f32 v4, v34, v36
	s_waitcnt lgkmcnt(0)
	v_cvt_pk_bf16_f32 v5, v38, v40
	v_lshl_add_u64 v[44:45], v[42:43], 0, v[44:45]
	v_add_u32_e32 v6, s11, v19
	global_store_dwordx4 v[44:45], v[2:5], off sc1
	s_add_i32 s6, s6, s33
	s_add_i32 s10, s10, s9
	v_cvt_pk_bf16_f32 v2, v7, v15
	v_ashrrev_i32_e32 v7, 31, v6
	v_lshlrev_b64 v[6:7], 11, v[6:7]
	v_cvt_pk_bf16_f32 v3, v31, v33
	v_cvt_pk_bf16_f32 v4, v35, v37
	v_cvt_pk_bf16_f32 v5, v39, v41
	v_lshl_add_u64 v[6:7], v[42:43], 0, v[6:7]
	s_cmpk_lt_i32 s6, 0x100
	v_add_u32_e32 v22, s7, v22
	global_store_dwordx4 v[6:7], v[2:5], off sc1
	s_barrier
	s_cbranch_scc0 .LBB0_164

.LBB0_169:
	s_or_b64 exec, exec, s[6:7]
	s_waitcnt vmcnt(0)
	ds_write2_b32 v30, v2, v3 offset1:1
	ds_write2_b32 v31, v4, v5 offset1:1
	s_waitcnt lgkmcnt(0)
	s_barrier
	ds_read2_b32 v[2:3], v21 offset1:65
	ds_read2_b32 v[4:5], v21 offset0:130 offset1:195
	v_add_u32_e32 v12, 0x400, v21
	ds_read2_b32 v[6:7], v12 offset0:4 offset1:69
	ds_read2_b32 v[16:17], v12 offset0:134 offset1:199
	s_lshl_b32 s6, s25, 10
	s_lshl_b32 s25, s25, 6
	s_sub_i32 s6, s24, s6
	s_waitcnt lgkmcnt(3)
	v_cvt_pk_bf16_f32 v2, v2, v3
	s_waitcnt lgkmcnt(2)
	v_cvt_pk_bf16_f32 v3, v4, v5
	s_waitcnt lgkmcnt(1)
	v_cvt_pk_bf16_f32 v4, v6, v7
	v_add_u32_e32 v6, s25, v18
	s_ashr_i32 s7, s6, 31
	v_ashrrev_i32_e32 v7, 31, v6
	v_add_u32_e32 v12, 0x400, v22
	v_lshl_add_u64 v[34:35], s[6:7], 1, v[14:15]
	s_waitcnt lgkmcnt(0)
	v_cvt_pk_bf16_f32 v5, v16, v17
	v_lshlrev_b64 v[6:7], 11, v[6:7]
	ds_read2_b32 v[16:17], v22 offset1:65
	ds_read2_b32 v[36:37], v22 offset0:130 offset1:195
	ds_read2_b32 v[38:39], v12 offset0:4 offset1:69
	ds_read2_b32 v[40:41], v12 offset0:134 offset1:199
	v_lshl_add_u64 v[6:7], v[34:35], 0, v[6:7]
	global_store_dwordx4 v[6:7], v[2:5], off sc1
	v_add_u32_e32 v6, s25, v19
	v_ashrrev_i32_e32 v7, 31, v6
	v_lshlrev_b64 v[6:7], 11, v[6:7]
	s_add_i32 s23, s23, s33
	s_add_i32 s24, s24, s9
	s_waitcnt lgkmcnt(3)
	v_cvt_pk_bf16_f32 v2, v16, v17
	s_waitcnt lgkmcnt(2)
	v_cvt_pk_bf16_f32 v3, v36, v37
	s_waitcnt lgkmcnt(1)
	v_cvt_pk_bf16_f32 v4, v38, v39
	s_waitcnt lgkmcnt(0)
	v_cvt_pk_bf16_f32 v5, v40, v41
	v_lshl_add_u64 v[6:7], v[34:35], 0, v[6:7]
	s_cmpk_lt_i32 s23, 0x580
	v_add_u32_e32 v33, s20, v33
	global_store_dwordx4 v[6:7], v[2:5], off sc1
	s_barrier
	s_cbranch_scc0 .LBB0_178

.LBB0_180:
	s_or_b64 exec, exec, s[4:5]
	v_add_u32_e32 v12, 0x400, v21
	s_waitcnt vmcnt(0)
	ds_write2_b32 v30, v2, v3 offset1:1
	ds_write2_b32 v31, v4, v5 offset1:1
	s_waitcnt lgkmcnt(0)
	s_barrier
	ds_read2_b32 v[2:3], v21 offset1:65
	ds_read2_b32 v[4:5], v21 offset0:130 offset1:195
	ds_read2_b32 v[6:7], v12 offset0:4 offset1:69
	ds_read2_b32 v[16:17], v12 offset0:134 offset1:199
	s_mul_i32 s4, s23, 0xfffff500
	v_add_u32_e32 v12, 0x400, v22
	s_add_i32 s4, s7, s4
	s_waitcnt lgkmcnt(3)
	v_cvt_pk_bf16_f32 v2, v2, v3
	s_waitcnt lgkmcnt(2)
	v_cvt_pk_bf16_f32 v3, v4, v5
	s_waitcnt lgkmcnt(0)
	v_cvt_pk_bf16_f32 v5, v16, v17
	ds_read2_b32 v[16:17], v22 offset1:65
	ds_read2_b32 v[36:37], v22 offset0:130 offset1:195
	ds_read2_b32 v[38:39], v12 offset0:4 offset1:69
	ds_read2_b32 v[40:41], v12 offset0:134 offset1:199
	s_lshl_b32 s23, s23, 6
	s_ashr_i32 s5, s4, 31
	v_lshl_add_u64 v[34:35], s[4:5], 1, v[14:15]
	v_cvt_pk_bf16_f32 v4, v6, v7
	v_add_u32_e32 v6, s23, v18
	v_mad_i64_i32 v[6:7], s[4:5], v6, s11, v[34:35]
	global_store_dwordx4 v[6:7], v[2:5], off sc1
	v_add_u32_e32 v6, s23, v19
	s_add_i32 s6, s6, s33
	s_add_i32 s7, s7, s9
	s_waitcnt lgkmcnt(3)
	v_cvt_pk_bf16_f32 v2, v16, v17
	s_waitcnt lgkmcnt(2)
	v_cvt_pk_bf16_f32 v3, v36, v37
	s_waitcnt lgkmcnt(1)
	v_cvt_pk_bf16_f32 v4, v38, v39
	s_waitcnt lgkmcnt(0)
	v_cvt_pk_bf16_f32 v5, v40, v41
	v_mad_i64_i32 v[6:7], s[4:5], v6, s11, v[34:35]
	s_cmpk_lt_i32 s6, 0x2c0
	v_add_u32_e32 v33, v33, v20
	global_store_dwordx4 v[6:7], v[2:5], off sc1
	s_barrier
	s_cbranch_scc0 .LBB0_166

.LBB0_189:
	s_cmp_gt_i32 s17, 1
	s_cselect_b64 s[0:1], -1, 0
	s_and_b64 s[4:5], s[18:19], s[0:1]
	s_andn2_b64 vcc, exec, s[4:5]
	v_lshrrev_b32_e32 v200, 20, v0
	v_lshrrev_b32_e32 v201, 10, v0
	s_cbranch_vccnz .LBB0_201
	s_waitcnt vmcnt(0)
	v_or_b32_e32 v0, v201, v200
	s_movk_i32 s3, 0x3ff
	v_and_or_b32 v0, v0, s3, v199
	v_cmp_eq_u32_e32 vcc, 0, v0
	s_barrier
	s_and_saveexec_b64 s[4:5], vcc
	s_cbranch_execz .LBB0_200
	s_add_u32 s6, s14, 0x5be8c00
	s_addc_u32 s7, s15, 0
	s_lshl_b32 s3, s2, 1
	v_mov_b32_e32 v0, s3
	v_mov_b32_e32 v1, 0x9301
	global_store_short v0, v1, s[6:7] sc1
	s_cmp_lg_u32 s2, 0
	s_cbranch_scc1 .Lgbar_wait_0
	s_lshr_b32 s3, s33, 3
	s_bfm_b64 s[8:9], s3, 0
	s_cmpk_gt_u32 s33, 0x1ff
	s_cselect_b64 s[8:9], -1, s[8:9]
	s_mov_b64 exec, -1
	v_mbcnt_lo_u32_b32 v229, -1, 0
	v_mbcnt_hi_u32_b32 v229, -1, v229
	v_lshlrev_b32_e32 v229, 4, v229
	s_mov_b32 s10, 0x93019301
	s_mov_b64 exec, s[8:9]

.LBB0_209:
	s_or_b64 exec, exec, s[6:7]
	v_ashrrev_i32_e32 v1, 12, v2
	v_mad_i32_i24 v1, v1, s35, s35
	v_cndmask_b32_e64 v34, v1, 0, s[4:5]
	v_ashrrev_i32_e32 v35, 31, v34
	v_lshl_add_u64 v[42:43], v[34:35], 2, s[14:15]
	v_lshl_add_u64 v[54:55], v[42:43], 0, s[28:29]
	v_lshl_add_u64 v[46:47], v[24:25], 0, v[12:13]
	v_lshl_add_u64 v[24:25], v[54:55], 0, v[12:13]
	s_waitcnt lgkmcnt(0)
	v_readfirstlane_b32 s4, v4
	v_readfirstlane_b32 s5, v5
	global_load_dwordx4 v[34:37], v[46:47], off
	s_nop 3
	global_load_dwordx4 v[38:41], v12, s[4:5]
	global_load_dwordx4 v[42:45], v[24:25], off
	v_lshlrev_b64 v[24:25], 12, v[22:23]
	v_lshlrev_b64 v[22:23], 11, v[22:23]
	v_lshl_add_u64 v[58:59], v[6:7], 0, v[24:25]
	v_lshl_add_u64 v[62:63], v[8:9], 0, v[22:23]
	v_lshl_add_u64 v[50:51], v[54:55], 0, v[16:17]
	s_waitcnt vmcnt(2)
	global_store_dwordx4 v[58:59], v[34:37], off sc1
	s_waitcnt vmcnt(2)
	v_pk_mul_f32 v[22:23], v[36:37], v[40:41]
	v_pk_mul_f32 v[24:25], v[34:35], v[38:39]
	s_waitcnt vmcnt(1)
	v_pk_add_f32 v[38:39], v[42:43], 1.0 op_sel_hi:[1,0]
	v_pk_add_f32 v[40:41], v[44:45], 1.0 op_sel_hi:[1,0]
	v_pk_mul_f32 v[24:25], v[38:39], v[24:25]
	v_pk_mul_f32 v[22:23], v[40:41], v[22:23]
	v_cvt_pk_bf16_f32 v24, v24, v25
	v_cvt_pk_bf16_f32 v25, v22, v23
	global_store_dwordx2 v[62:63], v[24:25], off sc1
	v_lshl_add_u64 v[42:43], v[54:55], 0, v[14:15]
	global_load_dwordx4 v[22:25], v[46:47], off offset:1024
	global_load_dwordx4 v[38:41], v12, s[4:5] offset:1024
	v_mul_f32_e32 v1, v35, v35
	global_load_dwordx4 v[42:45], v[42:43], off
	v_fmac_f32_e32 v1, v34, v34
	v_fmac_f32_e32 v1, v36, v36
	v_fmac_f32_e32 v1, v37, v37
	s_waitcnt vmcnt(2)
	global_store_dwordx4 v[58:59], v[22:25], off offset:1024 sc1
	s_waitcnt vmcnt(2)
	v_pk_mul_f32 v[40:41], v[24:25], v[40:41]
	v_pk_mul_f32 v[38:39], v[22:23], v[38:39]
	s_waitcnt vmcnt(1)
	v_pk_add_f32 v[42:43], v[42:43], 1.0 op_sel_hi:[1,0]
	v_pk_add_f32 v[44:45], v[44:45], 1.0 op_sel_hi:[1,0]
	v_pk_mul_f32 v[38:39], v[42:43], v[38:39]
	v_pk_mul_f32 v[40:41], v[44:45], v[40:41]
	v_cvt_pk_bf16_f32 v38, v38, v39
	v_cvt_pk_bf16_f32 v39, v40, v41
	global_store_dwordx2 v[62:63], v[38:39], off offset:512 sc1
	global_load_dwordx4 v[38:41], v[46:47], off offset:2048
	s_nop 0
	global_load_dwordx4 v[42:45], v12, s[4:5] offset:2048
	v_mul_f32_e32 v2, v23, v23
	global_load_dwordx4 v[50:53], v[50:51], off
	v_fmac_f32_e32 v2, v22, v22
	v_fmac_f32_e32 v2, v24, v24
	v_fmac_f32_e32 v2, v25, v25
	v_add_f32_e32 v1, v1, v2
	s_waitcnt vmcnt(2)
	global_store_dwordx4 v[58:59], v[38:41], off offset:2048 sc1
	s_waitcnt vmcnt(2)
	v_pk_mul_f32 v[44:45], v[40:41], v[44:45]
	v_pk_mul_f32 v[42:43], v[38:39], v[42:43]
	s_waitcnt vmcnt(1)
	v_pk_add_f32 v[50:51], v[50:51], 1.0 op_sel_hi:[1,0]
	v_pk_add_f32 v[52:53], v[52:53], 1.0 op_sel_hi:[1,0]
	v_pk_mul_f32 v[42:43], v[50:51], v[42:43]
	v_pk_mul_f32 v[44:45], v[52:53], v[44:45]
	v_cvt_pk_bf16_f32 v42, v42, v43
	v_cvt_pk_bf16_f32 v43, v44, v45
	global_store_dwordx2 v[62:63], v[42:43], off offset:1024 sc1
	global_load_dwordx4 v[42:45], v[46:47], off offset:3072
	s_nop 0
	global_load_dwordx4 v[50:53], v12, s[4:5] offset:3072
	v_lshl_add_u64 v[46:47], v[54:55], 0, v[18:19]
	global_load_dwordx4 v[54:57], v[46:47], off
	v_mul_f32_e32 v2, v39, v39
	v_fmac_f32_e32 v2, v38, v38
	v_fmac_f32_e32 v2, v40, v40
	v_fmac_f32_e32 v2, v41, v41
	v_add_f32_e32 v1, v1, v2
	s_waitcnt vmcnt(2)
	v_mul_f32_e32 v2, v43, v43
	v_fmac_f32_e32 v2, v42, v42
	v_fmac_f32_e32 v2, v44, v44
	v_fmac_f32_e32 v2, v45, v45
	v_add_f32_e32 v1, v1, v2
	ds_bpermute_b32 v2, v26, v1
	s_waitcnt vmcnt(1)
	v_pk_mul_f32 v[24:25], v[42:43], v[50:51]
	s_waitcnt vmcnt(0)
	v_pk_add_f32 v[34:35], v[54:55], 1.0 op_sel_hi:[1,0]
	v_pk_mul_f32 v[22:23], v[44:45], v[52:53]
	v_pk_mul_f32 v[24:25], v[34:35], v[24:25]
	s_waitcnt lgkmcnt(0)
	v_add_f32_e32 v1, v1, v2
	ds_bpermute_b32 v2, v27, v1
	v_pk_add_f32 v[34:35], v[56:57], 1.0 op_sel_hi:[1,0]
	v_cvt_pk_bf16_f32 v24, v24, v25
	v_pk_mul_f32 v[22:23], v[34:35], v[22:23]
	global_store_dwordx4 v[58:59], v[42:45], off offset:3072 sc1
	s_waitcnt lgkmcnt(0)
	v_add_f32_e32 v1, v1, v2
	ds_bpermute_b32 v2, v28, v1
	v_cvt_pk_bf16_f32 v25, v22, v23
	global_store_dwordx2 v[62:63], v[24:25], off offset:1536 sc1
	s_waitcnt lgkmcnt(0)
	v_add_f32_e32 v1, v1, v2
	ds_bpermute_b32 v2, v29, v1
	s_waitcnt lgkmcnt(0)
	v_add_f32_e32 v1, v1, v2
	ds_bpermute_b32 v2, v30, v1
	s_waitcnt lgkmcnt(0)
	v_add_f32_e32 v1, v1, v2
	ds_bpermute_b32 v2, v31, v1
	s_and_saveexec_b64 s[4:5], vcc
	s_cbranch_execz .LBB0_204
	v_add_u32_e32 v22, v32, v20
	v_ashrrev_i32_e32 v23, 31, v22
	s_waitcnt lgkmcnt(0)
	v_add_f32_e32 v1, v1, v2
	v_lshl_add_u64 v[22:23], v[22:23], 2, s[22:23]
	v_cndmask_b32_e64 v1, 0, v1, s[0:1]
	global_store_dword v[22:23], v1, off sc1
	s_branch .LBB0_204

.LBB0_214:
	v_lshl_add_u64 v[72:73], s[14:15], 0, v[54:55]
	s_waitcnt lgkmcnt(1)
	global_load_dwordx4 v[64:67], v[72:73], off
	s_waitcnt lgkmcnt(0)
	global_load_dwordx4 v[68:71], v[72:73], off offset:16
	s_waitcnt vmcnt(1)
	v_lshlrev_b32_e32 v63, 16, v64
	v_and_b32_e32 v64, 0xffff0000, v64
	v_lshlrev_b32_e32 v72, 16, v65
	v_and_b32_e32 v65, 0xffff0000, v65
	v_mul_f32_e32 v79, v9, v64
	v_mul_f32_e32 v80, v25, v64
	v_mul_f32_e32 v64, v41, v64
	v_lshlrev_b32_e32 v73, 16, v66
	v_and_b32_e32 v66, 0xffff0000, v66
	v_mul_f32_e32 v81, v11, v65
	v_mul_f32_e32 v82, v27, v65
	v_mul_f32_e32 v65, v43, v65
	v_fmac_f32_e32 v79, v8, v63
	v_fmac_f32_e32 v80, v24, v63
	v_fmac_f32_e32 v64, v40, v63
	v_lshlrev_b32_e32 v74, 16, v67
	v_and_b32_e32 v67, 0xffff0000, v67
	v_mul_f32_e32 v83, v1, v66
	v_mul_f32_e32 v84, v17, v66
	v_mul_f32_e32 v66, v33, v66
	v_fmac_f32_e32 v81, v10, v72
	v_fmac_f32_e32 v82, v26, v72
	v_fmac_f32_e32 v65, v42, v72
	v_add_f32_e32 v63, 0, v79
	v_add_f32_e32 v72, 0, v80
	v_add_f32_e32 v64, 0, v64
	s_waitcnt vmcnt(0)
	v_lshlrev_b32_e32 v75, 16, v68
	v_and_b32_e32 v68, 0xffff0000, v68
	v_mul_f32_e32 v85, v3, v67
	v_mul_f32_e32 v86, v19, v67
	v_mul_f32_e32 v67, v35, v67
	v_fmac_f32_e32 v83, v0, v73
	v_fmac_f32_e32 v84, v16, v73
	v_fmac_f32_e32 v66, v32, v73
	v_add_f32_e32 v63, v63, v81
	v_add_f32_e32 v72, v72, v82
	v_add_f32_e32 v64, v64, v65
	v_lshlrev_b32_e32 v76, 16, v69
	v_and_b32_e32 v69, 0xffff0000, v69
	v_mul_f32_e32 v87, v5, v68
	v_mul_f32_e32 v88, v21, v68
	v_mul_f32_e32 v68, v37, v68
	v_fmac_f32_e32 v85, v2, v74
	v_fmac_f32_e32 v86, v18, v74
	v_fmac_f32_e32 v67, v34, v74
	v_add_f32_e32 v63, v63, v83
	v_add_f32_e32 v65, v72, v84
	v_add_f32_e32 v64, v64, v66
	v_lshlrev_b32_e32 v77, 16, v70
	v_and_b32_e32 v70, 0xffff0000, v70
	v_mul_f32_e32 v89, v7, v69
	v_mul_f32_e32 v90, v23, v69
	v_mul_f32_e32 v69, v39, v69
	v_fmac_f32_e32 v87, v4, v75
	v_fmac_f32_e32 v88, v20, v75
	v_fmac_f32_e32 v68, v36, v75
	v_add_f32_e32 v63, v63, v85
	v_add_f32_e32 v65, v65, v86
	v_add_f32_e32 v64, v64, v67
	v_lshlrev_b32_e32 v78, 16, v71
	v_and_b32_e32 v71, 0xffff0000, v71
	v_mul_f32_e32 v91, v13, v70
	v_mul_f32_e32 v92, v29, v70
	v_mul_f32_e32 v70, v45, v70
	v_fmac_f32_e32 v89, v6, v76
	v_fmac_f32_e32 v90, v22, v76
	v_fmac_f32_e32 v69, v38, v76
	v_add_f32_e32 v63, v63, v87
	v_add_f32_e32 v65, v65, v88
	v_add_f32_e32 v64, v64, v68
	v_mul_f32_e32 v93, v15, v71
	v_mul_f32_e32 v94, v31, v71
	v_mul_f32_e32 v71, v47, v71
	v_fmac_f32_e32 v91, v12, v77
	v_fmac_f32_e32 v92, v28, v77
	v_fmac_f32_e32 v70, v44, v77
	v_add_f32_e32 v63, v63, v89
	v_add_f32_e32 v65, v65, v90
	v_add_f32_e32 v64, v64, v69
	v_fmac_f32_e32 v93, v14, v78
	v_fmac_f32_e32 v94, v30, v78
	v_fmac_f32_e32 v71, v46, v78
	v_add_f32_e32 v63, v63, v91
	v_add_f32_e32 v65, v65, v92
	v_add_f32_e32 v64, v64, v70
	v_add_f32_e32 v63, v63, v93
	v_add_f32_e32 v65, v65, v94
	v_add_f32_e32 v64, v64, v71
	ds_bpermute_b32 v66, v51, v63
	ds_bpermute_b32 v67, v51, v65
	ds_bpermute_b32 v68, v51, v64
	s_waitcnt lgkmcnt(2)
	v_add_f32_e32 v63, v63, v66
	s_waitcnt lgkmcnt(1)
	v_add_f32_e32 v65, v65, v67
	s_waitcnt lgkmcnt(0)
	v_add_f32_e32 v64, v64, v68
	ds_bpermute_b32 v66, v56, v63
	ds_bpermute_b32 v67, v56, v65
	ds_bpermute_b32 v68, v56, v64
	s_waitcnt lgkmcnt(2)
	v_add_f32_e32 v63, v63, v66
	s_waitcnt lgkmcnt(1)
	v_add_f32_e32 v65, v65, v67
	s_waitcnt lgkmcnt(0)
	v_add_f32_e32 v64, v64, v68
	ds_bpermute_b32 v66, v57, v63
	ds_bpermute_b32 v67, v57, v65
	ds_bpermute_b32 v68, v57, v64
	s_waitcnt lgkmcnt(2)
	v_add_f32_e32 v63, v63, v66
	s_waitcnt lgkmcnt(1)
	v_add_f32_e32 v65, v65, v67
	s_waitcnt lgkmcnt(0)
	v_add_f32_e32 v64, v64, v68
	ds_bpermute_b32 v66, v58, v63
	ds_bpermute_b32 v67, v58, v65
	ds_bpermute_b32 v68, v58, v64
	s_waitcnt lgkmcnt(2)
	v_add_f32_e32 v63, v63, v66
	s_waitcnt lgkmcnt(1)
	v_add_f32_e32 v65, v65, v67
	s_waitcnt lgkmcnt(0)
	v_add_f32_e32 v66, v64, v68
	ds_bpermute_b32 v64, v59, v63
	ds_bpermute_b32 v67, v59, v65
	ds_bpermute_b32 v68, v59, v66
	s_waitcnt lgkmcnt(2)
	v_add_f32_e32 v63, v63, v64
	s_waitcnt lgkmcnt(1)
	v_add_f32_e32 v64, v65, v67
	s_waitcnt lgkmcnt(0)
	v_add_f32_e32 v66, v66, v68
	ds_bpermute_b32 v65, v61, v63
	ds_bpermute_b32 v67, v61, v64
	ds_bpermute_b32 v68, v61, v66
	s_and_saveexec_b64 s[24:25], s[0:1]
	s_cbranch_execz .LBB0_213
	s_waitcnt lgkmcnt(1)
	v_add_f32_e32 v69, v64, v67
	v_add_f32_e32 v63, v63, v65
	v_lshl_add_u64 v[64:65], s[14:15], 0, v[52:53]
	s_waitcnt lgkmcnt(0)
	v_add_f32_e32 v68, v66, v68
	v_add_co_u32_e32 v66, vcc, 0x5be8000, v64
	s_nop 1
	v_addc_co_u32_e32 v67, vcc, 0, v65, vcc
	global_store_dword v[66:67], v63, off sc1
	v_add_co_u32_e32 v66, vcc, 0x5beb000, v64
	s_nop 1
	v_addc_co_u32_e32 v67, vcc, 0, v65, vcc
	v_add_co_u32_e32 v64, vcc, 0x5bee000, v64
	global_store_dword v[66:67], v69, off sc1
	s_nop 0
	v_addc_co_u32_e32 v65, vcc, 0, v65, vcc
	global_store_dword v[64:65], v68, off sc1
	s_branch .LBB0_213

.LBB0_219:
	s_waitcnt lgkmcnt(0)
	v_lshl_add_u64 v[68:69], s[14:15], 0, v[54:55]
	v_add_co_u32_e32 v64, vcc, 0x5a0000, v68
	s_nop 1
	v_addc_co_u32_e32 v65, vcc, 0, v69, vcc
	global_load_dwordx4 v[64:67], v[64:65], off
	v_lshl_add_u64 v[68:69], v[68:69], 0, s[24:25]
	global_load_dwordx4 v[68:71], v[68:69], off offset:16
	s_waitcnt vmcnt(1)
	v_lshlrev_b32_e32 v63, 16, v64
	v_and_b32_e32 v64, 0xffff0000, v64
	v_lshlrev_b32_e32 v72, 16, v65
	v_and_b32_e32 v65, 0xffff0000, v65
	v_mul_f32_e32 v79, v9, v64
	v_mul_f32_e32 v80, v25, v64
	v_mul_f32_e32 v64, v41, v64
	v_lshlrev_b32_e32 v73, 16, v66
	v_and_b32_e32 v66, 0xffff0000, v66
	v_mul_f32_e32 v81, v11, v65
	v_mul_f32_e32 v82, v27, v65
	v_mul_f32_e32 v65, v43, v65
	v_fmac_f32_e32 v79, v8, v63
	v_fmac_f32_e32 v80, v24, v63
	v_fmac_f32_e32 v64, v40, v63
	v_lshlrev_b32_e32 v74, 16, v67
	v_and_b32_e32 v67, 0xffff0000, v67
	v_mul_f32_e32 v83, v1, v66
	v_mul_f32_e32 v84, v17, v66
	v_mul_f32_e32 v66, v33, v66
	v_fmac_f32_e32 v81, v10, v72
	v_fmac_f32_e32 v82, v26, v72
	v_fmac_f32_e32 v65, v42, v72
	v_add_f32_e32 v63, 0, v79
	v_add_f32_e32 v72, 0, v80
	v_add_f32_e32 v64, 0, v64
	s_waitcnt vmcnt(0)
	v_lshlrev_b32_e32 v75, 16, v68
	v_and_b32_e32 v68, 0xffff0000, v68
	v_mul_f32_e32 v85, v3, v67
	v_mul_f32_e32 v86, v19, v67
	v_mul_f32_e32 v67, v35, v67
	v_fmac_f32_e32 v83, v0, v73
	v_fmac_f32_e32 v84, v16, v73
	v_fmac_f32_e32 v66, v32, v73
	v_add_f32_e32 v63, v63, v81
	v_add_f32_e32 v72, v72, v82
	v_add_f32_e32 v64, v64, v65
	v_lshlrev_b32_e32 v76, 16, v69
	v_and_b32_e32 v69, 0xffff0000, v69
	v_mul_f32_e32 v87, v5, v68
	v_mul_f32_e32 v88, v21, v68
	v_mul_f32_e32 v68, v37, v68
	v_fmac_f32_e32 v85, v2, v74
	v_fmac_f32_e32 v86, v18, v74
	v_fmac_f32_e32 v67, v34, v74
	v_add_f32_e32 v63, v63, v83
	v_add_f32_e32 v65, v72, v84
	v_add_f32_e32 v64, v64, v66
	v_lshlrev_b32_e32 v77, 16, v70
	v_and_b32_e32 v70, 0xffff0000, v70
	v_mul_f32_e32 v89, v7, v69
	v_mul_f32_e32 v90, v23, v69
	v_mul_f32_e32 v69, v39, v69
	v_fmac_f32_e32 v87, v4, v75
	v_fmac_f32_e32 v88, v20, v75
	v_fmac_f32_e32 v68, v36, v75
	v_add_f32_e32 v63, v63, v85
	v_add_f32_e32 v65, v65, v86
	v_add_f32_e32 v64, v64, v67
	v_lshlrev_b32_e32 v78, 16, v71
	v_and_b32_e32 v71, 0xffff0000, v71
	v_mul_f32_e32 v91, v13, v70
	v_mul_f32_e32 v92, v29, v70
	v_mul_f32_e32 v70, v45, v70
	v_fmac_f32_e32 v89, v6, v76
	v_fmac_f32_e32 v90, v22, v76
	v_fmac_f32_e32 v69, v38, v76
	v_add_f32_e32 v63, v63, v87
	v_add_f32_e32 v65, v65, v88
	v_add_f32_e32 v64, v64, v68
	v_mul_f32_e32 v93, v15, v71
	v_mul_f32_e32 v94, v31, v71
	v_fmac_f32_e32 v91, v12, v77
	v_fmac_f32_e32 v92, v28, v77
	v_fmac_f32_e32 v70, v44, v77
	v_add_f32_e32 v63, v63, v89
	v_add_f32_e32 v65, v65, v90
	v_add_f32_e32 v64, v64, v69
	v_mul_f32_e32 v66, v47, v71
	v_fmac_f32_e32 v93, v14, v78
	v_fmac_f32_e32 v94, v30, v78
	v_add_f32_e32 v63, v63, v91
	v_add_f32_e32 v65, v65, v92
	v_add_f32_e32 v64, v64, v70
	v_fmac_f32_e32 v66, v46, v78
	v_add_f32_e32 v63, v63, v93
	v_add_f32_e32 v65, v65, v94
	v_add_f32_e32 v64, v64, v66
	ds_bpermute_b32 v67, v51, v63
	ds_bpermute_b32 v68, v51, v65
	ds_bpermute_b32 v66, v51, v64
	s_waitcnt lgkmcnt(2)
	v_add_f32_e32 v63, v63, v67
	s_waitcnt lgkmcnt(1)
	v_add_f32_e32 v65, v65, v68
	s_waitcnt lgkmcnt(0)
	v_add_f32_e32 v64, v64, v66
	ds_bpermute_b32 v67, v56, v63
	ds_bpermute_b32 v68, v56, v65
	ds_bpermute_b32 v66, v56, v64
	s_waitcnt lgkmcnt(2)
	v_add_f32_e32 v63, v63, v67
	s_waitcnt lgkmcnt(1)
	v_add_f32_e32 v65, v65, v68
	s_waitcnt lgkmcnt(0)
	v_add_f32_e32 v64, v64, v66
	ds_bpermute_b32 v67, v57, v63
	ds_bpermute_b32 v68, v57, v65
	ds_bpermute_b32 v66, v57, v64
	s_waitcnt lgkmcnt(2)
	v_add_f32_e32 v63, v63, v67
	s_waitcnt lgkmcnt(1)
	v_add_f32_e32 v65, v65, v68
	s_waitcnt lgkmcnt(0)
	v_add_f32_e32 v64, v64, v66
	ds_bpermute_b32 v67, v58, v63
	ds_bpermute_b32 v68, v58, v65
	ds_bpermute_b32 v66, v58, v64
	s_waitcnt lgkmcnt(2)
	v_add_f32_e32 v63, v63, v67
	s_waitcnt lgkmcnt(1)
	v_add_f32_e32 v65, v65, v68
	s_waitcnt lgkmcnt(0)
	v_add_f32_e32 v69, v64, v66
	ds_bpermute_b32 v67, v59, v63
	ds_bpermute_b32 v68, v59, v65
	ds_bpermute_b32 v70, v59, v69
	s_waitcnt lgkmcnt(2)
	v_add_f32_e32 v63, v63, v67
	s_waitcnt lgkmcnt(1)
	v_add_f32_e32 v65, v65, v68
	s_waitcnt lgkmcnt(0)
	v_add_f32_e32 v67, v69, v70
	ds_bpermute_b32 v64, v61, v63
	ds_bpermute_b32 v66, v61, v65
	ds_bpermute_b32 v68, v61, v67
	s_and_saveexec_b64 s[26:27], s[0:1]
	s_cbranch_execz .LBB0_218
	s_waitcnt lgkmcnt(1)
	v_add_f32_e32 v69, v65, v66
	v_add_f32_e32 v63, v63, v64
	v_lshl_add_u64 v[64:65], s[14:15], 0, v[52:53]
	v_add_co_u32_e32 v66, vcc, 0x5bf1000, v64
	s_waitcnt lgkmcnt(0)
	v_add_f32_e32 v68, v67, v68
	v_addc_co_u32_e32 v67, vcc, 0, v65, vcc
	global_store_dword v[66:67], v63, off sc1
	v_add_co_u32_e32 v66, vcc, 0x5bf4000, v64
	s_nop 1
	v_addc_co_u32_e32 v67, vcc, 0, v65, vcc
	v_add_co_u32_e32 v64, vcc, 0x5bf7000, v64
	global_store_dword v[66:67], v69, off sc1
	s_nop 0
	v_addc_co_u32_e32 v65, vcc, 0, v65, vcc
	global_store_dword v[64:65], v68, off sc1
	s_branch .LBB0_218

.LBB0_224:
	s_waitcnt lgkmcnt(0)
	v_lshl_add_u64 v[68:69], s[14:15], 0, v[54:55]
	v_add_co_u32_e32 v64, vcc, 0xda0000, v68
	s_nop 1
	v_addc_co_u32_e32 v65, vcc, 0, v69, vcc
	global_load_dwordx4 v[64:67], v[64:65], off
	v_lshl_add_u64 v[68:69], v[68:69], 0, s[24:25]
	global_load_dwordx4 v[68:71], v[68:69], off offset:16
	s_waitcnt vmcnt(1)
	v_lshlrev_b32_e32 v63, 16, v64
	v_and_b32_e32 v64, 0xffff0000, v64
	v_lshlrev_b32_e32 v72, 16, v65
	v_and_b32_e32 v65, 0xffff0000, v65
	v_mul_f32_e32 v79, v9, v64
	v_mul_f32_e32 v80, v25, v64
	v_mul_f32_e32 v64, v41, v64
	v_lshlrev_b32_e32 v73, 16, v66
	v_and_b32_e32 v66, 0xffff0000, v66
	v_mul_f32_e32 v81, v11, v65
	v_mul_f32_e32 v82, v27, v65
	v_mul_f32_e32 v65, v43, v65
	v_fmac_f32_e32 v79, v8, v63
	v_fmac_f32_e32 v80, v24, v63
	v_fmac_f32_e32 v64, v40, v63
	v_lshlrev_b32_e32 v74, 16, v67
	v_and_b32_e32 v67, 0xffff0000, v67
	v_mul_f32_e32 v83, v1, v66
	v_mul_f32_e32 v84, v17, v66
	v_mul_f32_e32 v66, v33, v66
	v_fmac_f32_e32 v81, v10, v72
	v_fmac_f32_e32 v82, v26, v72
	v_fmac_f32_e32 v65, v42, v72
	v_add_f32_e32 v63, 0, v79
	v_add_f32_e32 v72, 0, v80
	v_add_f32_e32 v64, 0, v64
	s_waitcnt vmcnt(0)
	v_lshlrev_b32_e32 v75, 16, v68
	v_and_b32_e32 v68, 0xffff0000, v68
	v_mul_f32_e32 v85, v3, v67
	v_mul_f32_e32 v86, v19, v67
	v_mul_f32_e32 v67, v35, v67
	v_fmac_f32_e32 v83, v0, v73
	v_fmac_f32_e32 v84, v16, v73
	v_fmac_f32_e32 v66, v32, v73
	v_add_f32_e32 v63, v63, v81
	v_add_f32_e32 v72, v72, v82
	v_add_f32_e32 v64, v64, v65
	v_lshlrev_b32_e32 v76, 16, v69
	v_and_b32_e32 v69, 0xffff0000, v69
	v_mul_f32_e32 v87, v5, v68
	v_mul_f32_e32 v88, v21, v68
	v_mul_f32_e32 v68, v37, v68
	v_fmac_f32_e32 v85, v2, v74
	v_fmac_f32_e32 v86, v18, v74
	v_fmac_f32_e32 v67, v34, v74
	v_add_f32_e32 v63, v63, v83
	v_add_f32_e32 v65, v72, v84
	v_add_f32_e32 v64, v64, v66
	v_lshlrev_b32_e32 v77, 16, v70
	v_and_b32_e32 v70, 0xffff0000, v70
	v_mul_f32_e32 v89, v7, v69
	v_mul_f32_e32 v90, v23, v69
	v_mul_f32_e32 v69, v39, v69
	v_fmac_f32_e32 v87, v4, v75
	v_fmac_f32_e32 v88, v20, v75
	v_fmac_f32_e32 v68, v36, v75
	v_add_f32_e32 v63, v63, v85
	v_add_f32_e32 v65, v65, v86
	v_add_f32_e32 v64, v64, v67
	v_lshlrev_b32_e32 v78, 16, v71
	v_and_b32_e32 v71, 0xffff0000, v71
	v_mul_f32_e32 v91, v13, v70
	v_mul_f32_e32 v92, v29, v70
	v_mul_f32_e32 v70, v45, v70
	v_fmac_f32_e32 v89, v6, v76
	v_fmac_f32_e32 v90, v22, v76
	v_fmac_f32_e32 v69, v38, v76
	v_add_f32_e32 v63, v63, v87
	v_add_f32_e32 v65, v65, v88
	v_add_f32_e32 v64, v64, v68
	v_mul_f32_e32 v93, v15, v71
	v_mul_f32_e32 v94, v31, v71
	v_fmac_f32_e32 v91, v12, v77
	v_fmac_f32_e32 v92, v28, v77
	v_fmac_f32_e32 v70, v44, v77
	v_add_f32_e32 v63, v63, v89
	v_add_f32_e32 v65, v65, v90
	v_add_f32_e32 v64, v64, v69
	v_mul_f32_e32 v66, v47, v71
	v_fmac_f32_e32 v93, v14, v78
	v_fmac_f32_e32 v94, v30, v78
	v_add_f32_e32 v63, v63, v91
	v_add_f32_e32 v65, v65, v92
	v_add_f32_e32 v64, v64, v70
	v_fmac_f32_e32 v66, v46, v78
	v_add_f32_e32 v63, v63, v93
	v_add_f32_e32 v65, v65, v94
	v_add_f32_e32 v64, v64, v66
	ds_bpermute_b32 v67, v51, v63
	ds_bpermute_b32 v68, v51, v65
	ds_bpermute_b32 v66, v51, v64
	s_waitcnt lgkmcnt(2)
	v_add_f32_e32 v63, v63, v67
	s_waitcnt lgkmcnt(1)
	v_add_f32_e32 v65, v65, v68
	s_waitcnt lgkmcnt(0)
	v_add_f32_e32 v64, v64, v66
	ds_bpermute_b32 v67, v56, v63
	ds_bpermute_b32 v68, v56, v65
	ds_bpermute_b32 v66, v56, v64
	s_waitcnt lgkmcnt(2)
	v_add_f32_e32 v63, v63, v67
	s_waitcnt lgkmcnt(1)
	v_add_f32_e32 v65, v65, v68
	s_waitcnt lgkmcnt(0)
	v_add_f32_e32 v64, v64, v66
	ds_bpermute_b32 v67, v57, v63
	ds_bpermute_b32 v68, v57, v65
	ds_bpermute_b32 v66, v57, v64
	s_waitcnt lgkmcnt(2)
	v_add_f32_e32 v63, v63, v67
	s_waitcnt lgkmcnt(1)
	v_add_f32_e32 v65, v65, v68
	s_waitcnt lgkmcnt(0)
	v_add_f32_e32 v64, v64, v66
	ds_bpermute_b32 v67, v58, v63
	ds_bpermute_b32 v68, v58, v65
	ds_bpermute_b32 v66, v58, v64
	s_waitcnt lgkmcnt(2)
	v_add_f32_e32 v63, v63, v67
	s_waitcnt lgkmcnt(1)
	v_add_f32_e32 v65, v65, v68
	s_waitcnt lgkmcnt(0)
	v_add_f32_e32 v69, v64, v66
	ds_bpermute_b32 v67, v59, v63
	ds_bpermute_b32 v68, v59, v65
	ds_bpermute_b32 v70, v59, v69
	s_waitcnt lgkmcnt(2)
	v_add_f32_e32 v63, v63, v67
	s_waitcnt lgkmcnt(1)
	v_add_f32_e32 v65, v65, v68
	s_waitcnt lgkmcnt(0)
	v_add_f32_e32 v67, v69, v70
	ds_bpermute_b32 v64, v61, v63
	ds_bpermute_b32 v66, v61, v65
	ds_bpermute_b32 v68, v61, v67
	s_and_saveexec_b64 s[26:27], s[0:1]
	s_cbranch_execz .LBB0_223
	s_waitcnt lgkmcnt(1)
	v_add_f32_e32 v69, v65, v66
	v_add_f32_e32 v63, v63, v64
	v_lshl_add_u64 v[64:65], s[14:15], 0, v[52:53]
	v_add_co_u32_e32 v66, vcc, 0x5bfa000, v64
	s_waitcnt lgkmcnt(0)
	v_add_f32_e32 v68, v67, v68
	v_addc_co_u32_e32 v67, vcc, 0, v65, vcc
	global_store_dword v[66:67], v63, off sc1
	v_add_co_u32_e32 v66, vcc, 0x5bfd000, v64
	s_nop 1
	v_addc_co_u32_e32 v67, vcc, 0, v65, vcc
	v_add_co_u32_e32 v64, vcc, 0x5c00000, v64
	global_store_dword v[66:67], v69, off sc1
	s_nop 0
	v_addc_co_u32_e32 v65, vcc, 0, v65, vcc
	global_store_dword v[64:65], v68, off sc1
	s_branch .LBB0_223

.LBB0_231:
	s_waitcnt lgkmcnt(0)
	v_lshl_add_u64 v[70:71], s[14:15], 0, v[52:53]
	v_add_co_u32_e32 v66, vcc, 0x12a0000, v70
	s_nop 1
	v_addc_co_u32_e32 v67, vcc, 0, v71, vcc
	global_load_dwordx4 v[66:69], v[66:67], off
	v_lshl_add_u64 v[70:71], v[70:71], 0, s[24:25]
	global_load_dwordx4 v[70:73], v[70:71], off offset:16
	s_waitcnt vmcnt(1)
	v_lshlrev_b32_e32 v74, 16, v66
	v_and_b32_e32 v66, 0xffff0000, v66
	v_lshlrev_b32_e32 v75, 16, v67
	v_and_b32_e32 v67, 0xffff0000, v67
	v_mul_f32_e32 v82, v9, v66
	v_mul_f32_e32 v83, v25, v66
	v_mul_f32_e32 v66, v41, v66
	v_lshlrev_b32_e32 v76, 16, v68
	v_and_b32_e32 v68, 0xffff0000, v68
	v_mul_f32_e32 v84, v11, v67
	v_mul_f32_e32 v85, v27, v67
	v_mul_f32_e32 v67, v43, v67
	v_fmac_f32_e32 v82, v8, v74
	v_fmac_f32_e32 v83, v24, v74
	v_fmac_f32_e32 v66, v40, v74
	v_lshlrev_b32_e32 v77, 16, v69
	v_and_b32_e32 v69, 0xffff0000, v69
	v_mul_f32_e32 v86, v1, v68
	v_mul_f32_e32 v87, v17, v68
	v_mul_f32_e32 v68, v33, v68
	v_fmac_f32_e32 v84, v10, v75
	v_fmac_f32_e32 v85, v26, v75
	v_fmac_f32_e32 v67, v42, v75
	v_add_f32_e32 v74, 0, v82
	v_add_f32_e32 v75, 0, v83
	v_add_f32_e32 v66, 0, v66
	s_waitcnt vmcnt(0)
	v_lshlrev_b32_e32 v78, 16, v70
	v_and_b32_e32 v70, 0xffff0000, v70
	v_mul_f32_e32 v88, v3, v69
	v_mul_f32_e32 v89, v19, v69
	v_mul_f32_e32 v69, v35, v69
	v_fmac_f32_e32 v86, v0, v76
	v_fmac_f32_e32 v87, v16, v76
	v_fmac_f32_e32 v68, v32, v76
	v_add_f32_e32 v74, v74, v84
	v_add_f32_e32 v75, v75, v85
	v_add_f32_e32 v66, v66, v67
	v_lshlrev_b32_e32 v79, 16, v71
	v_and_b32_e32 v71, 0xffff0000, v71
	v_mul_f32_e32 v90, v5, v70
	v_mul_f32_e32 v91, v21, v70
	v_mul_f32_e32 v70, v37, v70
	v_fmac_f32_e32 v88, v2, v77
	v_fmac_f32_e32 v89, v18, v77
	v_fmac_f32_e32 v69, v34, v77
	v_add_f32_e32 v67, v74, v86
	v_add_f32_e32 v74, v75, v87
	v_add_f32_e32 v66, v66, v68
	v_lshlrev_b32_e32 v80, 16, v72
	v_and_b32_e32 v72, 0xffff0000, v72
	v_mul_f32_e32 v92, v7, v71
	v_mul_f32_e32 v93, v23, v71
	v_mul_f32_e32 v71, v39, v71
	v_fmac_f32_e32 v90, v4, v78
	v_fmac_f32_e32 v91, v20, v78
	v_fmac_f32_e32 v70, v36, v78
	v_add_f32_e32 v67, v67, v88
	v_add_f32_e32 v68, v74, v89
	v_add_f32_e32 v66, v66, v69
	v_lshlrev_b32_e32 v81, 16, v73
	v_and_b32_e32 v73, 0xffff0000, v73
	v_mul_f32_e32 v94, v13, v72
	v_mul_f32_e32 v95, v29, v72
	v_mul_f32_e32 v72, v45, v72
	v_fmac_f32_e32 v92, v6, v79
	v_fmac_f32_e32 v93, v22, v79
	v_fmac_f32_e32 v71, v38, v79
	v_add_f32_e32 v67, v67, v90
	v_add_f32_e32 v68, v68, v91
	v_add_f32_e32 v66, v66, v70
	v_mul_f32_e32 v96, v15, v73
	v_mul_f32_e32 v97, v31, v73
	v_fmac_f32_e32 v94, v12, v80
	v_fmac_f32_e32 v95, v28, v80
	v_fmac_f32_e32 v72, v44, v80
	v_add_f32_e32 v67, v67, v92
	v_add_f32_e32 v68, v68, v93
	v_add_f32_e32 v66, v66, v71
	v_mul_f32_e32 v69, v47, v73
	v_fmac_f32_e32 v96, v14, v81
	v_fmac_f32_e32 v97, v30, v81
	v_add_f32_e32 v67, v67, v94
	v_add_f32_e32 v68, v68, v95
	v_add_f32_e32 v66, v66, v72
	v_fmac_f32_e32 v69, v46, v81
	v_add_f32_e32 v67, v67, v96
	v_add_f32_e32 v68, v68, v97
	v_add_f32_e32 v66, v66, v69
	ds_bpermute_b32 v70, v51, v67
	ds_bpermute_b32 v71, v51, v68
	ds_bpermute_b32 v69, v51, v66
	s_waitcnt lgkmcnt(2)
	v_add_f32_e32 v67, v67, v70
	s_waitcnt lgkmcnt(1)
	v_add_f32_e32 v68, v68, v71
	s_waitcnt lgkmcnt(0)
	v_add_f32_e32 v66, v66, v69
	ds_bpermute_b32 v70, v61, v67
	ds_bpermute_b32 v71, v61, v68
	ds_bpermute_b32 v69, v61, v66
	s_waitcnt lgkmcnt(2)
	v_add_f32_e32 v67, v67, v70
	s_waitcnt lgkmcnt(1)
	v_add_f32_e32 v68, v68, v71
	s_waitcnt lgkmcnt(0)
	v_add_f32_e32 v66, v66, v69
	ds_bpermute_b32 v70, v62, v67
	ds_bpermute_b32 v71, v62, v68
	ds_bpermute_b32 v69, v62, v66
	s_waitcnt lgkmcnt(2)
	v_add_f32_e32 v67, v67, v70
	s_waitcnt lgkmcnt(1)
	v_add_f32_e32 v68, v68, v71
	s_waitcnt lgkmcnt(0)
	v_add_f32_e32 v66, v66, v69
	ds_bpermute_b32 v70, v63, v67
	ds_bpermute_b32 v71, v63, v68
	ds_bpermute_b32 v69, v63, v66
	s_waitcnt lgkmcnt(2)
	v_add_f32_e32 v67, v67, v70
	s_waitcnt lgkmcnt(1)
	v_add_f32_e32 v68, v68, v71
	s_waitcnt lgkmcnt(0)
	v_add_f32_e32 v72, v66, v69
	ds_bpermute_b32 v70, v64, v67
	ds_bpermute_b32 v71, v64, v68
	ds_bpermute_b32 v73, v64, v72
	s_waitcnt lgkmcnt(2)
	v_add_f32_e32 v66, v67, v70
	s_waitcnt lgkmcnt(1)
	v_add_f32_e32 v68, v68, v71
	s_waitcnt lgkmcnt(0)
	v_add_f32_e32 v70, v72, v73
	ds_bpermute_b32 v67, v65, v66
	ds_bpermute_b32 v69, v65, v68
	ds_bpermute_b32 v71, v65, v70
	s_and_saveexec_b64 s[26:27], s[0:1]
	s_cbranch_execz .LBB0_230
	s_waitcnt lgkmcnt(2)
	v_add_f32_e32 v72, v66, v67
	v_lshl_add_u64 v[66:67], s[14:15], 0, v[54:55]
	s_waitcnt lgkmcnt(0)
	v_add_f32_e32 v70, v70, v71
	v_add_f32_e32 v71, v68, v69
	v_add_co_u32_e32 v68, vcc, 0x5c03000, v66
	s_nop 1
	v_addc_co_u32_e32 v69, vcc, 0, v67, vcc
	global_store_dword v[68:69], v72, off sc1
	v_add_co_u32_e32 v68, vcc, 0x5c06000, v66
	s_nop 1
	v_addc_co_u32_e32 v69, vcc, 0, v67, vcc
	v_add_co_u32_e32 v66, vcc, 0x5c09000, v66
	global_store_dword v[68:69], v71, off sc1
	s_nop 0
	v_addc_co_u32_e32 v67, vcc, 0, v67, vcc
	global_store_dword v[66:67], v70, off sc1
	s_branch .LBB0_230

.LBB0_239:
	s_waitcnt lgkmcnt(2)
	global_load_dwordx4 v[78:81], v[60:61], off offset:-16
	s_waitcnt lgkmcnt(0)
	global_load_dwordx4 v[82:85], v[60:61], off
	s_waitcnt vmcnt(1)
	v_lshlrev_b32_e32 v86, 16, v78
	v_and_b32_e32 v78, 0xffff0000, v78
	v_lshlrev_b32_e32 v87, 16, v79
	v_and_b32_e32 v79, 0xffff0000, v79
	v_mul_f32_e32 v94, v9, v78
	v_mul_f32_e32 v95, v25, v78
	v_mul_f32_e32 v78, v41, v78
	v_lshlrev_b32_e32 v88, 16, v80
	v_and_b32_e32 v80, 0xffff0000, v80
	v_mul_f32_e32 v96, v11, v79
	v_mul_f32_e32 v97, v27, v79
	v_mul_f32_e32 v79, v43, v79
	v_fmac_f32_e32 v94, v8, v86
	v_fmac_f32_e32 v95, v24, v86
	v_fmac_f32_e32 v78, v40, v86
	v_lshlrev_b32_e32 v89, 16, v81
	v_and_b32_e32 v81, 0xffff0000, v81
	v_mul_f32_e32 v98, v1, v80
	v_mul_f32_e32 v99, v17, v80
	v_mul_f32_e32 v80, v33, v80
	v_fmac_f32_e32 v96, v10, v87
	v_fmac_f32_e32 v97, v26, v87
	v_fmac_f32_e32 v79, v42, v87
	v_add_f32_e32 v86, 0, v94
	v_add_f32_e32 v87, 0, v95
	v_add_f32_e32 v78, 0, v78
	s_waitcnt vmcnt(0)
	v_lshlrev_b32_e32 v90, 16, v82
	v_and_b32_e32 v82, 0xffff0000, v82
	v_mul_f32_e32 v100, v3, v81
	v_mul_f32_e32 v101, v19, v81
	v_mul_f32_e32 v81, v35, v81
	v_fmac_f32_e32 v98, v0, v88
	v_fmac_f32_e32 v99, v16, v88
	v_fmac_f32_e32 v80, v32, v88
	v_add_f32_e32 v86, v86, v96
	v_add_f32_e32 v87, v87, v97
	v_add_f32_e32 v78, v78, v79
	v_lshlrev_b32_e32 v91, 16, v83
	v_and_b32_e32 v83, 0xffff0000, v83
	v_mul_f32_e32 v102, v5, v82
	v_mul_f32_e32 v103, v21, v82
	v_mul_f32_e32 v82, v37, v82
	v_fmac_f32_e32 v100, v2, v89
	v_fmac_f32_e32 v101, v18, v89
	v_fmac_f32_e32 v81, v34, v89
	v_add_f32_e32 v79, v86, v98
	v_add_f32_e32 v86, v87, v99
	v_add_f32_e32 v78, v78, v80
	v_lshlrev_b32_e32 v92, 16, v84
	v_and_b32_e32 v84, 0xffff0000, v84
	v_mul_f32_e32 v104, v7, v83
	v_mul_f32_e32 v105, v23, v83
	v_mul_f32_e32 v83, v39, v83
	v_fmac_f32_e32 v102, v4, v90
	v_fmac_f32_e32 v103, v20, v90
	v_fmac_f32_e32 v82, v36, v90
	v_add_f32_e32 v79, v79, v100
	v_add_f32_e32 v80, v86, v101
	v_add_f32_e32 v78, v78, v81
	v_lshlrev_b32_e32 v93, 16, v85
	v_and_b32_e32 v85, 0xffff0000, v85
	v_mul_f32_e32 v106, v13, v84
	v_mul_f32_e32 v107, v29, v84
	v_mul_f32_e32 v84, v45, v84
	v_fmac_f32_e32 v104, v6, v91
	v_fmac_f32_e32 v105, v22, v91
	v_fmac_f32_e32 v83, v38, v91
	v_add_f32_e32 v79, v79, v102
	v_add_f32_e32 v80, v80, v103
	v_add_f32_e32 v78, v78, v82
	v_mul_f32_e32 v108, v15, v85
	v_mul_f32_e32 v109, v31, v85
	v_mul_f32_e32 v85, v47, v85
	v_fmac_f32_e32 v106, v12, v92
	v_fmac_f32_e32 v107, v28, v92
	v_fmac_f32_e32 v84, v44, v92
	v_add_f32_e32 v79, v79, v104
	v_add_f32_e32 v80, v80, v105
	v_add_f32_e32 v78, v78, v83
	v_fmac_f32_e32 v108, v14, v93
	v_fmac_f32_e32 v109, v30, v93
	v_fmac_f32_e32 v85, v46, v93
	v_add_f32_e32 v79, v79, v106
	v_add_f32_e32 v80, v80, v107
	v_add_f32_e32 v78, v78, v84
	v_add_f32_e32 v79, v79, v108
	v_add_f32_e32 v80, v80, v109
	v_add_f32_e32 v78, v78, v85
	ds_bpermute_b32 v81, v71, v79
	ds_bpermute_b32 v82, v71, v80
	ds_bpermute_b32 v83, v71, v78
	s_waitcnt lgkmcnt(2)
	v_add_f32_e32 v79, v79, v81
	s_waitcnt lgkmcnt(1)
	v_add_f32_e32 v80, v80, v82
	s_waitcnt lgkmcnt(0)
	v_add_f32_e32 v78, v78, v83
	ds_bpermute_b32 v81, v72, v79
	ds_bpermute_b32 v82, v72, v80
	ds_bpermute_b32 v83, v72, v78
	s_waitcnt lgkmcnt(2)
	v_add_f32_e32 v79, v79, v81
	s_waitcnt lgkmcnt(1)
	v_add_f32_e32 v80, v80, v82
	s_waitcnt lgkmcnt(0)
	v_add_f32_e32 v78, v78, v83
	ds_bpermute_b32 v81, v73, v79
	ds_bpermute_b32 v82, v73, v80
	ds_bpermute_b32 v83, v73, v78
	s_waitcnt lgkmcnt(2)
	v_add_f32_e32 v79, v79, v81
	s_waitcnt lgkmcnt(1)
	v_add_f32_e32 v80, v80, v82
	s_waitcnt lgkmcnt(0)
	v_add_f32_e32 v78, v78, v83
	ds_bpermute_b32 v81, v74, v79
	ds_bpermute_b32 v82, v74, v80
	ds_bpermute_b32 v83, v74, v78
	s_waitcnt lgkmcnt(2)
	v_add_f32_e32 v79, v79, v81
	s_waitcnt lgkmcnt(1)
	v_add_f32_e32 v80, v80, v82
	s_waitcnt lgkmcnt(0)
	v_add_f32_e32 v81, v78, v83
	ds_bpermute_b32 v78, v75, v79
	ds_bpermute_b32 v82, v75, v80
	ds_bpermute_b32 v83, v75, v81
	s_waitcnt lgkmcnt(2)
	v_add_f32_e32 v78, v79, v78
	s_waitcnt lgkmcnt(1)
	v_add_f32_e32 v79, v80, v82
	s_waitcnt lgkmcnt(0)
	v_add_f32_e32 v81, v81, v83
	ds_bpermute_b32 v80, v76, v78
	ds_bpermute_b32 v82, v76, v79
	ds_bpermute_b32 v83, v76, v81
	s_and_saveexec_b64 s[36:37], s[4:5]
	s_cbranch_execz .LBB0_238
	s_waitcnt lgkmcnt(2)
	v_add_f32_e32 v78, v78, v80
	global_store_dword v[62:63], v78, off sc1
	v_add_co_u32_e32 v78, vcc, 0x5000, v62
	s_waitcnt lgkmcnt(1)
	v_add_f32_e32 v82, v79, v82
	v_addc_co_u32_e32 v79, vcc, 0, v63, vcc
	global_store_dword v[78:79], v82, off offset:2048 sc1
	v_add_co_u32_e32 v78, vcc, 0xb000, v62
	s_waitcnt lgkmcnt(0)
	v_add_f32_e32 v81, v81, v83
	v_addc_co_u32_e32 v79, vcc, 0, v63, vcc
	global_store_dword v[78:79], v81, off sc1
	s_branch .LBB0_238
.LBB0_241:
	s_cmp_gt_i32 s17, 2
	s_cselect_b64 s[0:1], -1, 0
	s_and_b64 s[4:5], s[8:9], s[0:1]
	s_andn2_b64 vcc, exec, s[4:5]
	s_cbranch_vccnz .LBB0_253
	s_waitcnt vmcnt(0)
	v_or_b32_e32 v0, v201, v200
	s_movk_i32 s3, 0x3ff
	v_and_or_b32 v0, v0, s3, v199
	v_cmp_eq_u32_e32 vcc, 0, v0
	s_waitcnt lgkmcnt(0)
	s_barrier
	s_and_saveexec_b64 s[4:5], vcc
	s_cbranch_execz .LBB0_252
	s_add_u32 s6, s14, 0x5be8c00
	s_addc_u32 s7, s15, 0
	s_lshl_b32 s3, s2, 1
	v_mov_b32_e32 v0, s3
	v_mov_b32_e32 v1, 0x9302
	global_store_short v0, v1, s[6:7] sc1
	s_cmp_lg_u32 s2, 0
	s_cbranch_scc1 .Lgbar_wait_1
	s_lshr_b32 s3, s33, 3
	s_bfm_b64 s[8:9], s3, 0
	s_cmpk_gt_u32 s33, 0x1ff
	s_cselect_b64 s[8:9], -1, s[8:9]
	s_mov_b64 exec, -1
	v_mbcnt_lo_u32_b32 v229, -1, 0
	v_mbcnt_hi_u32_b32 v229, -1, v229
	v_lshlrev_b32_e32 v229, 4, v229
	s_mov_b32 s10, 0x93029302
	s_mov_b64 exec, s[8:9]

.LBB0_253:
	s_cmp_lt_i32 s16, 3
	s_cselect_b64 s[6:7], -1, 0
	s_and_b64 s[0:1], s[6:7], s[0:1]
	s_andn2_b64 vcc, exec, s[0:1]
	s_cbranch_vccnz .LBB0_538
	s_ashr_i32 s0, s2, 31
	s_and_b32 s0, s0, s33
	s_add_i32 s3, s0, s2
	v_writelane_b32 v228, s88, 0
	s_cmpk_gt_i32 s3, 0x2ff
	s_nop 0
	v_writelane_b32 v228, s89, 1
	s_cbranch_scc1 .LBB0_529
	s_add_u32 s18, s14, 0x5c4e000
	s_addc_u32 s19, s15, 0
	s_add_u32 s84, s14, 0x5be8000
	s_addc_u32 s85, s15, 0
	s_add_u32 s20, s14, 0x609f000
	s_addc_u32 s21, s15, 0
	s_add_u32 s22, s14, 0xdf9f000
	s_addc_u32 s23, s15, 0
	s_add_u32 s24, s12, 0x4800000
	s_addc_u32 s25, s13, 0
	s_add_u32 s26, s14, 0x13e1f000
	s_addc_u32 s27, s15, 0
	s_add_u32 s28, s12, 0x4000000
	s_addc_u32 s29, s13, 0
	v_lshrrev_b32_e32 v1, 5, v199
	v_bfe_u32 v4, v199, 1, 3
	s_add_u32 s30, s14, 0x607e000
	v_lshrrev_b32_e32 v0, 3, v199
	v_bfe_u32 v2, v199, 5, 1
	v_lshrrev_b32_e32 v3, 1, v199
	v_lshlrev_b32_e32 v5, 4, v199
	v_bitop3_b32 v1, v1, v4, 1 bitop3:0x6c
	s_addc_u32 s31, s15, 0
	v_and_b32_e32 v156, 31, v199
	v_xor_b32_e32 v6, v5, v199
	v_lshlrev_b32_e32 v7, 11, v0
	s_movk_i32 s0, 0x70
	v_mov_b32_e32 v151, 0
	v_and_b32_e32 v3, 0x1e0, v3
	v_lshlrev_b32_e32 v168, 4, v1
	v_bitop3_b32 v1, v2, v4, 2 bitop3:0x36
	s_add_u32 s34, s14, 0x1321f000
	v_and_or_b32 v158, v6, s0, v7
	v_mov_b32_e32 v159, v151
	v_or_b32_e32 v6, v3, v156
	v_lshlrev_b32_e32 v170, 4, v1
	v_bitop3_b32 v1, v2, v4, 4 bitop3:0x36
	s_addc_u32 s35, s15, 0
	v_lshl_add_u32 v167, v6, 7, 0
	v_lshlrev_b32_e32 v171, 4, v1
	v_bitop3_b32 v1, v2, v4, 6 bitop3:0x36
	v_and_or_b32 v173, v0, 4, v3
	v_lshl_add_u64 v[160:161], s[14:15], 0, v[158:159]
	s_mov_b64 s[4:5], 0x679f000
	s_add_u32 s36, s14, 0x604e000
	v_add_u32_e32 v192, 0, v5
	v_mbcnt_lo_u32_b32 v0, -1, 0
	v_or_b32_e32 v166, 0xfffffe80, v156
	s_mov_b32 s9, 0
	v_lshl_add_u32 v169, v156, 7, 0
	v_lshlrev_b32_e32 v172, 4, v1
	v_mov_b32_e32 v157, v151
	v_or_b32_e32 v174, 0x80, v156
	v_or_b32_e32 v175, 0xa0, v156
	v_or_b32_e32 v176, 1, v173
	v_or_b32_e32 v177, 2, v173
	v_or_b32_e32 v178, 3, v173
	v_or_b32_e32 v179, 8, v173
	v_or_b32_e32 v180, 9, v173
	v_or_b32_e32 v181, 10, v173
	v_or_b32_e32 v182, 11, v173
	v_or_b32_e32 v183, 16, v173
	v_or_b32_e32 v184, 17, v173
	v_or_b32_e32 v185, 18, v173
	v_or_b32_e32 v186, 19, v173
	v_or_b32_e32 v187, 24, v173
	v_or_b32_e32 v188, 25, v173
	v_or_b32_e32 v189, 26, v173
	v_or_b32_e32 v190, 27, v173
	v_cmp_eq_u32_e64 s[0:1], 0, v156
	v_or_b32_e32 v191, 0xffff3a00, v173
	v_lshl_add_u64 v[162:163], v[160:161], 0, s[4:5]
	s_addc_u32 s37, s15, 0
	v_add_u32_e32 v193, 0x4000, v192
	s_mov_b64 s[38:39], 0x10000
	v_add_u32_e32 v194, 0x1000, v192
	v_add_u32_e32 v195, 0x5000, v192
	s_mov_b64 s[40:41], 0x20000
	v_add_u32_e32 v196, 0x2000, v192
	v_add_u32_e32 v197, 0x6000, v192
	s_mov_b64 s[42:43], 0x30000
	v_add_u32_e32 v198, 0x3000, v192
	v_add_u32_e32 v202, 0x7000, v192
	s_mov_b64 s[44:45], 0x679f080
	s_mov_b64 s[46:47], 0x80
	v_add_u32_e32 v203, 0x8000, v192
	v_add_u32_e32 v204, 0xc000, v192
	s_mov_b64 s[48:49], 0x67af080
	v_add_u32_e32 v205, 0x9000, v192
	s_mov_b64 s[50:51], 0x10080
	v_add_u32_e32 v206, 0xd000, v192
	s_mov_b64 s[52:53], 0x67bf080
	v_add_u32_e32 v207, 0xa000, v192
	s_mov_b64 s[54:55], 0x20080
	v_add_u32_e32 v208, 0xe000, v192
	s_mov_b64 s[56:57], 0x67cf080
	s_mov_b64 s[58:59], 0x30080
	s_mov_b64 s[60:61], 0x679f100
	s_mov_b64 s[62:63], 0x100
	s_mov_b64 s[64:65], 0x67af100
	s_mov_b64 s[66:67], 0x10100
	s_mov_b64 s[68:69], 0x67bf100
	s_mov_b64 s[70:71], 0x20100
	s_mov_b64 s[72:73], 0x67cf100
	s_mov_b64 s[74:75], 0x30100
	s_mov_b32 s86, 0x10000
	s_mov_b32 s87, 0x20000
	s_mov_b32 s88, 0x30000
	s_mov_b32 s89, 0x40000
	s_mov_b32 s90, 0x50000
	s_mov_b32 s91, 0x60000
	s_mov_b32 s92, 0x70000
	v_mov_b32_e32 v209, 0x358637bd
	s_add_i32 s93, 0, 0x120b0
	v_lshlrev_b32_e32 v210, 2, v156
	s_movk_i32 s94, 0x600
	s_add_i32 s96, 0, 0x12098
	s_add_i32 s97, 0, 0x12090
	v_add_u32_e32 v211, 0xb000, v192
	v_add_u32_e32 v212, 0xf000, v192
	v_add_u32_e32 v213, v167, v168
	v_mbcnt_hi_u32_b32 v214, -1, v0
	s_mov_b32 s57, 0
	s_branch .LBB0_258

.LBB0_258:
	s_mul_hi_i32 s4, s3, 0x2aaaaaab
	s_lshr_b32 s5, s4, 31
	s_ashr_i32 s4, s4, 3
	s_add_i32 s4, s4, s5
	s_mul_i32 s95, s4, 0xffffffd0
	s_add_i32 s95, s95, s3
	s_lshl_b32 s5, s4, 3
	s_ashr_i32 s4, s95, 31
	s_lshr_b32 s4, s4, 29
	s_add_i32 s4, s95, s4
	s_ashr_i32 s10, s4, 3
	s_and_b32 s4, s4, -8
	s_sub_i32 s8, s95, s4
	s_add_i32 s8, s8, s5
	s_lshl_b32 s76, s8, 7
	s_ashr_i32 s77, s76, 31
	s_lshl_b32 s78, s10, 7
	s_lshl_b64 s[4:5], s[76:77], 11
	s_ashr_i32 s79, s78, 31
	s_cmp_eq_u32 s57, 1
	s_cbranch_scc1 .Lgk_pfhead_p2
	s_lshl_b32 s56, s76, 11
	s_add_u32 s38, s14, s56
	s_addc_u32 s39, s15, 0
	s_add_u32 s38, s38, 0x679f000
	s_addc_u32 s39, s39, 0
	s_add_u32 s40, s38, 0x10000
	s_addc_u32 s41, s39, 0
	s_add_u32 s42, s40, 0x10000
	s_addc_u32 s43, s41, 0
	s_add_u32 s44, s42, 0x10000
	s_addc_u32 s45, s43, 0
	s_lshl_b32 s56, s78, 11
	s_add_u32 s46, s14, s56
	s_addc_u32 s47, s15, 0
	s_add_u32 s46, s46, 0x0
	s_addc_u32 s47, s47, 0
	s_add_u32 s48, s46, 0x10000
	s_addc_u32 s49, s47, 0
	s_add_u32 s50, s48, 0x10000
	s_addc_u32 s51, s49, 0
	s_add_u32 s52, s50, 0x10000
	s_addc_u32 s53, s51, 0
	v_add_u32_e32 v221, v169, v168
	v_add_u32_e32 v226, v167, v170
	v_add_u32_e32 v227, v169, v170
	v_add_u32_e32 v229, v167, v171
	v_add_u32_e32 v255, v169, v171
	v_add_u32_e32 v162, v167, v172
	v_add_u32_e32 v163, v169, v172
	v_readfirstlane_b32 s54, v192
	v_mov_b32_e32 v254, v158
	s_mov_b32 m0, s54
	s_nop 0
	global_load_lds_dwordx4 v254, s[38:39]
	s_add_u32 m0, m0, 0x1000
	s_nop 0
	global_load_lds_dwordx4 v254, s[40:41]
	s_add_u32 m0, m0, 0x1000
	s_nop 0
	global_load_lds_dwordx4 v254, s[42:43]
	s_add_u32 m0, m0, 0x1000
	s_nop 0
	global_load_lds_dwordx4 v254, s[44:45]
	s_add_u32 m0, m0, 0x1000
	s_nop 0
	global_load_lds_dwordx4 v254, s[46:47]
	s_add_u32 m0, m0, 0x1000
	s_nop 0
	global_load_lds_dwordx4 v254, s[48:49]
	s_add_u32 m0, m0, 0x1000
	s_nop 0
	global_load_lds_dwordx4 v254, s[50:51]
	s_add_u32 m0, m0, 0x1000
	s_nop 0
	global_load_lds_dwordx4 v254, s[52:53]
	v_add_u32_e32 v254, 0x80, v254
	s_add_u32 m0, s54, 0x8000
	s_nop 0
	global_load_lds_dwordx4 v254, s[38:39]
	s_add_u32 m0, m0, 0x1000
	s_nop 0
	global_load_lds_dwordx4 v254, s[40:41]
	s_add_u32 m0, m0, 0x1000
	s_nop 0
	global_load_lds_dwordx4 v254, s[42:43]
	s_add_u32 m0, m0, 0x1000
	s_nop 0
	global_load_lds_dwordx4 v254, s[44:45]
	s_add_u32 m0, m0, 0x1000
	s_nop 0
	global_load_lds_dwordx4 v254, s[46:47]
	s_add_u32 m0, m0, 0x1000
	s_nop 0
	global_load_lds_dwordx4 v254, s[48:49]
	s_add_u32 m0, m0, 0x1000
	s_nop 0
	global_load_lds_dwordx4 v254, s[50:51]
	s_add_u32 m0, m0, 0x1000
	s_nop 0
	global_load_lds_dwordx4 v254, s[52:53]
	v_add_u32_e32 v254, 0x80, v254
.Lgk_pfhead_p2:
	v_mov_b32_e32 v48, 0
	v_mov_b32_e32 v49, 0
	v_mov_b32_e32 v50, 0
	v_mov_b32_e32 v51, 0
	v_mov_b32_e32 v52, 0
	v_mov_b32_e32 v53, 0
	v_mov_b32_e32 v54, 0
	v_mov_b32_e32 v55, 0
	v_mov_b32_e32 v56, 0
	v_mov_b32_e32 v57, 0
	v_mov_b32_e32 v58, 0
	v_mov_b32_e32 v59, 0
	v_mov_b32_e32 v60, 0
	v_mov_b32_e32 v61, 0
	v_mov_b32_e32 v62, 0
	v_mov_b32_e32 v63, 0
	v_mov_b32_e32 v32, 0
	v_mov_b32_e32 v33, 0
	v_mov_b32_e32 v34, 0
	v_mov_b32_e32 v35, 0
	v_mov_b32_e32 v36, 0
	v_mov_b32_e32 v37, 0
	v_mov_b32_e32 v38, 0
	v_mov_b32_e32 v39, 0
	v_mov_b32_e32 v40, 0
	v_mov_b32_e32 v41, 0
	v_mov_b32_e32 v42, 0
	v_mov_b32_e32 v43, 0
	v_mov_b32_e32 v44, 0
	v_mov_b32_e32 v45, 0
	v_mov_b32_e32 v46, 0
	v_mov_b32_e32 v47, 0
	v_mov_b32_e32 v16, 0
	v_mov_b32_e32 v17, 0
	v_mov_b32_e32 v18, 0
	v_mov_b32_e32 v19, 0
	v_mov_b32_e32 v20, 0
	v_mov_b32_e32 v21, 0
	v_mov_b32_e32 v22, 0
	v_mov_b32_e32 v23, 0
	v_mov_b32_e32 v24, 0
	v_mov_b32_e32 v25, 0
	v_mov_b32_e32 v26, 0
	v_mov_b32_e32 v27, 0
	v_mov_b32_e32 v28, 0
	v_mov_b32_e32 v29, 0
	v_mov_b32_e32 v30, 0
	v_mov_b32_e32 v31, 0
	v_mov_b32_e32 v0, 0
	v_mov_b32_e32 v1, 0
	v_mov_b32_e32 v2, 0
	v_mov_b32_e32 v3, 0
	v_mov_b32_e32 v4, 0
	v_mov_b32_e32 v5, 0
	v_mov_b32_e32 v6, 0
	v_mov_b32_e32 v7, 0
	v_mov_b32_e32 v8, 0
	v_mov_b32_e32 v9, 0
	v_mov_b32_e32 v10, 0
	v_mov_b32_e32 v11, 0
	v_mov_b32_e32 v12, 0
	v_mov_b32_e32 v13, 0
	v_mov_b32_e32 v14, 0
	v_mov_b32_e32 v15, 0
	s_mov_b32 s55, 7
.Lgk_loop_p2:
	s_waitcnt vmcnt(8)
	s_barrier
	ds_read_b128 v[64:67], v213
	ds_read_b128 v[76:79], v221 offset:16384
	ds_read_b128 v[80:83], v221 offset:20480
	ds_read_b128 v[84:87], v221 offset:24576
	ds_read_b128 v[88:91], v221 offset:28672
	ds_read_b128 v[92:95], v226
	ds_read_b128 v[96:99], v227 offset:16384
	ds_read_b128 v[100:103], v227 offset:20480
	ds_read_b128 v[104:107], v227 offset:24576
	ds_read_b128 v[108:111], v227 offset:28672
	ds_read_b128 v[112:115], v229
	ds_read_b128 v[222:225], v255 offset:16384
	ds_read_b128 v[230:233], v255 offset:20480
	ds_read_b128 v[234:237], v255 offset:24576
	ds_read_b128 v[238:241], v255 offset:28672
	ds_read_b128 v[242:245], v162
	ds_read_b128 v[246:249], v163 offset:16384
	ds_read_b128 v[250:253], v163 offset:20480
	ds_read_b128 v[194:197], v163 offset:24576
	ds_read_b128 v[202:205], v163 offset:28672
	s_waitcnt lgkmcnt(0)
	s_barrier
	s_mov_b32 m0, s54
	s_setprio 1
	v_mfma_f32_32x32x16_bf16 v[48:63], v[64:67], v[76:79], v[48:63]
	v_mfma_f32_32x32x16_bf16 v[32:47], v[64:67], v[80:83], v[32:47]
	global_load_lds_dwordx4 v254, s[38:39]
	s_add_u32 m0, m0, 0x1000
	v_mfma_f32_32x32x16_bf16 v[16:31], v[64:67], v[84:87], v[16:31]
	v_mfma_f32_32x32x16_bf16 v[0:15], v[64:67], v[88:91], v[0:15]
	global_load_lds_dwordx4 v254, s[40:41]
	s_add_u32 m0, m0, 0x1000
	v_mfma_f32_32x32x16_bf16 v[48:63], v[92:95], v[96:99], v[48:63]
	v_mfma_f32_32x32x16_bf16 v[32:47], v[92:95], v[100:103], v[32:47]
	global_load_lds_dwordx4 v254, s[42:43]
	s_add_u32 m0, m0, 0x1000
	v_mfma_f32_32x32x16_bf16 v[16:31], v[92:95], v[104:107], v[16:31]
	v_mfma_f32_32x32x16_bf16 v[0:15], v[92:95], v[108:111], v[0:15]
	global_load_lds_dwordx4 v254, s[44:45]
	s_add_u32 m0, m0, 0x1000
	v_mfma_f32_32x32x16_bf16 v[48:63], v[112:115], v[222:225], v[48:63]
	v_mfma_f32_32x32x16_bf16 v[32:47], v[112:115], v[230:233], v[32:47]
	global_load_lds_dwordx4 v254, s[46:47]
	s_add_u32 m0, m0, 0x1000
	v_mfma_f32_32x32x16_bf16 v[16:31], v[112:115], v[234:237], v[16:31]
	v_mfma_f32_32x32x16_bf16 v[0:15], v[112:115], v[238:241], v[0:15]
	global_load_lds_dwordx4 v254, s[48:49]
	s_add_u32 m0, m0, 0x1000
	v_mfma_f32_32x32x16_bf16 v[48:63], v[242:245], v[246:249], v[48:63]
	v_mfma_f32_32x32x16_bf16 v[32:47], v[242:245], v[250:253], v[32:47]
	global_load_lds_dwordx4 v254, s[50:51]
	s_add_u32 m0, m0, 0x1000
	v_mfma_f32_32x32x16_bf16 v[16:31], v[242:245], v[194:197], v[16:31]
	v_mfma_f32_32x32x16_bf16 v[0:15], v[242:245], v[202:205], v[0:15]
	global_load_lds_dwordx4 v254, s[52:53]
	s_setprio 0
	v_add_u32_e32 v254, 0x80, v254
	s_waitcnt vmcnt(8)
	s_barrier
	ds_read_b128 v[64:67], v213 offset:32768
	ds_read_b128 v[76:79], v221 offset:49152
	ds_read_b128 v[80:83], v221 offset:53248
	ds_read_b128 v[84:87], v221 offset:57344
	ds_read_b128 v[88:91], v221 offset:61440
	ds_read_b128 v[92:95], v226 offset:32768
	ds_read_b128 v[96:99], v227 offset:49152
	ds_read_b128 v[100:103], v227 offset:53248
	ds_read_b128 v[104:107], v227 offset:57344
	ds_read_b128 v[108:111], v227 offset:61440
	ds_read_b128 v[112:115], v229 offset:32768
	ds_read_b128 v[222:225], v255 offset:49152
	ds_read_b128 v[230:233], v255 offset:53248
	ds_read_b128 v[234:237], v255 offset:57344
	ds_read_b128 v[238:241], v255 offset:61440
	ds_read_b128 v[242:245], v162 offset:32768
	ds_read_b128 v[246:249], v163 offset:49152
	ds_read_b128 v[250:253], v163 offset:53248
	ds_read_b128 v[194:197], v163 offset:57344
	ds_read_b128 v[202:205], v163 offset:61440
	s_waitcnt lgkmcnt(0)
	s_barrier
	s_add_u32 m0, s54, 0x8000
	s_setprio 1
	v_mfma_f32_32x32x16_bf16 v[48:63], v[64:67], v[76:79], v[48:63]
	v_mfma_f32_32x32x16_bf16 v[32:47], v[64:67], v[80:83], v[32:47]
	global_load_lds_dwordx4 v254, s[38:39]
	s_add_u32 m0, m0, 0x1000
	v_mfma_f32_32x32x16_bf16 v[16:31], v[64:67], v[84:87], v[16:31]
	v_mfma_f32_32x32x16_bf16 v[0:15], v[64:67], v[88:91], v[0:15]
	global_load_lds_dwordx4 v254, s[40:41]
	s_add_u32 m0, m0, 0x1000
	v_mfma_f32_32x32x16_bf16 v[48:63], v[92:95], v[96:99], v[48:63]
	v_mfma_f32_32x32x16_bf16 v[32:47], v[92:95], v[100:103], v[32:47]
	global_load_lds_dwordx4 v254, s[42:43]
	s_add_u32 m0, m0, 0x1000
	v_mfma_f32_32x32x16_bf16 v[16:31], v[92:95], v[104:107], v[16:31]
	v_mfma_f32_32x32x16_bf16 v[0:15], v[92:95], v[108:111], v[0:15]
	global_load_lds_dwordx4 v254, s[44:45]
	s_add_u32 m0, m0, 0x1000
	v_mfma_f32_32x32x16_bf16 v[48:63], v[112:115], v[222:225], v[48:63]
	v_mfma_f32_32x32x16_bf16 v[32:47], v[112:115], v[230:233], v[32:47]
	global_load_lds_dwordx4 v254, s[46:47]
	s_add_u32 m0, m0, 0x1000
	v_mfma_f32_32x32x16_bf16 v[16:31], v[112:115], v[234:237], v[16:31]
	v_mfma_f32_32x32x16_bf16 v[0:15], v[112:115], v[238:241], v[0:15]
	global_load_lds_dwordx4 v254, s[48:49]
	s_add_u32 m0, m0, 0x1000
	v_mfma_f32_32x32x16_bf16 v[48:63], v[242:245], v[246:249], v[48:63]
	v_mfma_f32_32x32x16_bf16 v[32:47], v[242:245], v[250:253], v[32:47]
	global_load_lds_dwordx4 v254, s[50:51]
	s_add_u32 m0, m0, 0x1000
	v_mfma_f32_32x32x16_bf16 v[16:31], v[242:245], v[194:197], v[16:31]
	v_mfma_f32_32x32x16_bf16 v[0:15], v[242:245], v[202:205], v[0:15]
	global_load_lds_dwordx4 v254, s[52:53]
	s_setprio 0
	v_add_u32_e32 v254, 0x80, v254
	s_sub_u32 s55, s55, 1
	s_cmp_lg_u32 s55, 0
	s_cbranch_scc1 .Lgk_loop_p2
	s_add_u32 s58, s3, s33
	s_cmp_gt_u32 s58, 0x2ff
	s_cbranch_scc1 .Lgk_tailplain_p2
.LBB0_258_pf_p2:
	s_mul_hi_i32 s60, s58, 0x2aaaaaab
	s_lshr_b32 s61, s60, 31
	s_ashr_i32 s60, s60, 3
	s_add_i32 s60, s60, s61
	s_mul_i32 s67, s60, 0xffffffd0
	s_add_i32 s67, s67, s58
	s_lshl_b32 s61, s60, 3
	s_ashr_i32 s60, s67, 31
	s_lshr_b32 s60, s60, 29
	s_add_i32 s60, s67, s60
	s_ashr_i32 s64, s60, 3
	s_and_b32 s60, s60, -8
	s_sub_i32 s59, s67, s60
	s_add_i32 s59, s59, s61
	s_lshl_b32 s62, s59, 7
	s_ashr_i32 s63, s62, 31
	s_lshl_b32 s65, s64, 7
	s_lshl_b64 s[60:61], s[62:63], 11
	s_ashr_i32 s66, s65, 31
	s_lshl_b32 s56, s62, 11
	s_add_u32 s38, s14, s56
	s_addc_u32 s39, s15, 0
	s_add_u32 s38, s38, 0x679f000
	s_addc_u32 s39, s39, 0
	s_add_u32 s40, s38, 0x10000
	s_addc_u32 s41, s39, 0
	s_add_u32 s42, s40, 0x10000
	s_addc_u32 s43, s41, 0
	s_add_u32 s44, s42, 0x10000
	s_addc_u32 s45, s43, 0
	s_lshl_b32 s56, s65, 11
	s_add_u32 s46, s14, s56
	s_addc_u32 s47, s15, 0
	s_add_u32 s46, s46, 0x0
	s_addc_u32 s47, s47, 0
	s_add_u32 s48, s46, 0x10000
	s_addc_u32 s49, s47, 0
	s_add_u32 s50, s48, 0x10000
	s_addc_u32 s51, s49, 0
	s_add_u32 s52, s50, 0x10000
	s_addc_u32 s53, s51, 0
	v_mov_b32_e32 v254, v158
	s_mov_b32 s57, 1
	s_waitcnt vmcnt(8)
	s_barrier
	ds_read_b128 v[64:67], v213
	ds_read_b128 v[76:79], v221 offset:16384
	ds_read_b128 v[80:83], v221 offset:20480
	ds_read_b128 v[84:87], v221 offset:24576
	ds_read_b128 v[88:91], v221 offset:28672
	ds_read_b128 v[92:95], v226
	ds_read_b128 v[96:99], v227 offset:16384
	ds_read_b128 v[100:103], v227 offset:20480
	ds_read_b128 v[104:107], v227 offset:24576
	ds_read_b128 v[108:111], v227 offset:28672
	ds_read_b128 v[112:115], v229
	ds_read_b128 v[222:225], v255 offset:16384
	ds_read_b128 v[230:233], v255 offset:20480
	ds_read_b128 v[234:237], v255 offset:24576
	ds_read_b128 v[238:241], v255 offset:28672
	ds_read_b128 v[242:245], v162
	ds_read_b128 v[246:249], v163 offset:16384
	ds_read_b128 v[250:253], v163 offset:20480
	ds_read_b128 v[194:197], v163 offset:24576
	ds_read_b128 v[202:205], v163 offset:28672
	s_waitcnt lgkmcnt(0)
	s_barrier
	s_mov_b32 m0, s54
	s_setprio 1
	v_mfma_f32_32x32x16_bf16 v[48:63], v[64:67], v[76:79], v[48:63]
	v_mfma_f32_32x32x16_bf16 v[32:47], v[64:67], v[80:83], v[32:47]
	global_load_lds_dwordx4 v254, s[38:39]
	s_add_u32 m0, m0, 0x1000
	v_mfma_f32_32x32x16_bf16 v[16:31], v[64:67], v[84:87], v[16:31]
	v_mfma_f32_32x32x16_bf16 v[0:15], v[64:67], v[88:91], v[0:15]
	global_load_lds_dwordx4 v254, s[40:41]
	s_add_u32 m0, m0, 0x1000
	v_mfma_f32_32x32x16_bf16 v[48:63], v[92:95], v[96:99], v[48:63]
	v_mfma_f32_32x32x16_bf16 v[32:47], v[92:95], v[100:103], v[32:47]
	global_load_lds_dwordx4 v254, s[42:43]
	s_add_u32 m0, m0, 0x1000
	v_mfma_f32_32x32x16_bf16 v[16:31], v[92:95], v[104:107], v[16:31]
	v_mfma_f32_32x32x16_bf16 v[0:15], v[92:95], v[108:111], v[0:15]
	global_load_lds_dwordx4 v254, s[44:45]
	s_add_u32 m0, m0, 0x1000
	v_mfma_f32_32x32x16_bf16 v[48:63], v[112:115], v[222:225], v[48:63]
	v_mfma_f32_32x32x16_bf16 v[32:47], v[112:115], v[230:233], v[32:47]
	global_load_lds_dwordx4 v254, s[46:47]
	s_add_u32 m0, m0, 0x1000
	v_mfma_f32_32x32x16_bf16 v[16:31], v[112:115], v[234:237], v[16:31]
	v_mfma_f32_32x32x16_bf16 v[0:15], v[112:115], v[238:241], v[0:15]
	global_load_lds_dwordx4 v254, s[48:49]
	s_add_u32 m0, m0, 0x1000
	v_mfma_f32_32x32x16_bf16 v[48:63], v[242:245], v[246:249], v[48:63]
	v_mfma_f32_32x32x16_bf16 v[32:47], v[242:245], v[250:253], v[32:47]
	global_load_lds_dwordx4 v254, s[50:51]
	s_add_u32 m0, m0, 0x1000
	v_mfma_f32_32x32x16_bf16 v[16:31], v[242:245], v[194:197], v[16:31]
	v_mfma_f32_32x32x16_bf16 v[0:15], v[242:245], v[202:205], v[0:15]
	global_load_lds_dwordx4 v254, s[52:53]
	s_setprio 0
	v_add_u32_e32 v254, 0x80, v254
	s_waitcnt vmcnt(8)
	s_barrier
	ds_read_b128 v[64:67], v213 offset:32768
	ds_read_b128 v[76:79], v221 offset:49152
	ds_read_b128 v[80:83], v221 offset:53248
	ds_read_b128 v[84:87], v221 offset:57344
	ds_read_b128 v[88:91], v221 offset:61440
	ds_read_b128 v[92:95], v226 offset:32768
	ds_read_b128 v[96:99], v227 offset:49152
	ds_read_b128 v[100:103], v227 offset:53248
	ds_read_b128 v[104:107], v227 offset:57344
	ds_read_b128 v[108:111], v227 offset:61440
	ds_read_b128 v[112:115], v229 offset:32768
	ds_read_b128 v[222:225], v255 offset:49152
	ds_read_b128 v[230:233], v255 offset:53248
	ds_read_b128 v[234:237], v255 offset:57344
	ds_read_b128 v[238:241], v255 offset:61440
	ds_read_b128 v[242:245], v162 offset:32768
	ds_read_b128 v[246:249], v163 offset:49152
	ds_read_b128 v[250:253], v163 offset:53248
	ds_read_b128 v[194:197], v163 offset:57344
	ds_read_b128 v[202:205], v163 offset:61440
	s_waitcnt lgkmcnt(0)
	s_barrier
	s_add_u32 m0, s54, 0x8000
	s_setprio 1
	v_mfma_f32_32x32x16_bf16 v[48:63], v[64:67], v[76:79], v[48:63]
	v_mfma_f32_32x32x16_bf16 v[32:47], v[64:67], v[80:83], v[32:47]
	global_load_lds_dwordx4 v254, s[38:39]
	s_add_u32 m0, m0, 0x1000
	v_mfma_f32_32x32x16_bf16 v[16:31], v[64:67], v[84:87], v[16:31]
	v_mfma_f32_32x32x16_bf16 v[0:15], v[64:67], v[88:91], v[0:15]
	global_load_lds_dwordx4 v254, s[40:41]
	s_add_u32 m0, m0, 0x1000
	v_mfma_f32_32x32x16_bf16 v[48:63], v[92:95], v[96:99], v[48:63]
	v_mfma_f32_32x32x16_bf16 v[32:47], v[92:95], v[100:103], v[32:47]
	global_load_lds_dwordx4 v254, s[42:43]
	s_add_u32 m0, m0, 0x1000
	v_mfma_f32_32x32x16_bf16 v[16:31], v[92:95], v[104:107], v[16:31]
	v_mfma_f32_32x32x16_bf16 v[0:15], v[92:95], v[108:111], v[0:15]
	global_load_lds_dwordx4 v254, s[44:45]
	s_add_u32 m0, m0, 0x1000
	v_mfma_f32_32x32x16_bf16 v[48:63], v[112:115], v[222:225], v[48:63]
	v_mfma_f32_32x32x16_bf16 v[32:47], v[112:115], v[230:233], v[32:47]
	global_load_lds_dwordx4 v254, s[46:47]
	s_add_u32 m0, m0, 0x1000
	v_mfma_f32_32x32x16_bf16 v[16:31], v[112:115], v[234:237], v[16:31]
	v_mfma_f32_32x32x16_bf16 v[0:15], v[112:115], v[238:241], v[0:15]
	global_load_lds_dwordx4 v254, s[48:49]
	s_add_u32 m0, m0, 0x1000
	v_mfma_f32_32x32x16_bf16 v[48:63], v[242:245], v[246:249], v[48:63]
	v_mfma_f32_32x32x16_bf16 v[32:47], v[242:245], v[250:253], v[32:47]
	global_load_lds_dwordx4 v254, s[50:51]
	s_add_u32 m0, m0, 0x1000
	v_mfma_f32_32x32x16_bf16 v[16:31], v[242:245], v[194:197], v[16:31]
	v_mfma_f32_32x32x16_bf16 v[0:15], v[242:245], v[202:205], v[0:15]
	global_load_lds_dwordx4 v254, s[52:53]
	s_setprio 0
	v_add_u32_e32 v254, 0x80, v254
	s_branch .LBB0_262
.Lgk_tailplain_p2:
	s_mov_b32 s57, 0
	s_waitcnt vmcnt(8)
	s_barrier
	ds_read_b128 v[64:67], v213
	ds_read_b128 v[76:79], v221 offset:16384
	ds_read_b128 v[80:83], v221 offset:20480
	ds_read_b128 v[84:87], v221 offset:24576
	ds_read_b128 v[88:91], v221 offset:28672
	ds_read_b128 v[92:95], v226
	ds_read_b128 v[96:99], v227 offset:16384
	ds_read_b128 v[100:103], v227 offset:20480
	ds_read_b128 v[104:107], v227 offset:24576
	ds_read_b128 v[108:111], v227 offset:28672
	ds_read_b128 v[112:115], v229
	ds_read_b128 v[222:225], v255 offset:16384
	ds_read_b128 v[230:233], v255 offset:20480
	ds_read_b128 v[234:237], v255 offset:24576
	ds_read_b128 v[238:241], v255 offset:28672
	ds_read_b128 v[242:245], v162
	ds_read_b128 v[246:249], v163 offset:16384
	ds_read_b128 v[250:253], v163 offset:20480
	ds_read_b128 v[194:197], v163 offset:24576
	ds_read_b128 v[202:205], v163 offset:28672
	s_waitcnt lgkmcnt(0)
	s_barrier
	s_setprio 1
	v_mfma_f32_32x32x16_bf16 v[48:63], v[64:67], v[76:79], v[48:63]
	v_mfma_f32_32x32x16_bf16 v[32:47], v[64:67], v[80:83], v[32:47]
	v_mfma_f32_32x32x16_bf16 v[16:31], v[64:67], v[84:87], v[16:31]
	v_mfma_f32_32x32x16_bf16 v[0:15], v[64:67], v[88:91], v[0:15]
	v_mfma_f32_32x32x16_bf16 v[48:63], v[92:95], v[96:99], v[48:63]
	v_mfma_f32_32x32x16_bf16 v[32:47], v[92:95], v[100:103], v[32:47]
	v_mfma_f32_32x32x16_bf16 v[16:31], v[92:95], v[104:107], v[16:31]
	v_mfma_f32_32x32x16_bf16 v[0:15], v[92:95], v[108:111], v[0:15]
	v_mfma_f32_32x32x16_bf16 v[48:63], v[112:115], v[222:225], v[48:63]
	v_mfma_f32_32x32x16_bf16 v[32:47], v[112:115], v[230:233], v[32:47]
	v_mfma_f32_32x32x16_bf16 v[16:31], v[112:115], v[234:237], v[16:31]
	v_mfma_f32_32x32x16_bf16 v[0:15], v[112:115], v[238:241], v[0:15]
	v_mfma_f32_32x32x16_bf16 v[48:63], v[242:245], v[246:249], v[48:63]
	v_mfma_f32_32x32x16_bf16 v[32:47], v[242:245], v[250:253], v[32:47]
	v_mfma_f32_32x32x16_bf16 v[16:31], v[242:245], v[194:197], v[16:31]
	v_mfma_f32_32x32x16_bf16 v[0:15], v[242:245], v[202:205], v[0:15]
	s_setprio 0
	s_waitcnt vmcnt(0)
	s_barrier
	ds_read_b128 v[64:67], v213 offset:32768
	ds_read_b128 v[76:79], v221 offset:49152
	ds_read_b128 v[80:83], v221 offset:53248
	ds_read_b128 v[84:87], v221 offset:57344
	ds_read_b128 v[88:91], v221 offset:61440
	ds_read_b128 v[92:95], v226 offset:32768
	ds_read_b128 v[96:99], v227 offset:49152
	ds_read_b128 v[100:103], v227 offset:53248
	ds_read_b128 v[104:107], v227 offset:57344
	ds_read_b128 v[108:111], v227 offset:61440
	ds_read_b128 v[112:115], v229 offset:32768
	ds_read_b128 v[222:225], v255 offset:49152
	ds_read_b128 v[230:233], v255 offset:53248
	ds_read_b128 v[234:237], v255 offset:57344
	ds_read_b128 v[238:241], v255 offset:61440
	ds_read_b128 v[242:245], v162 offset:32768
	ds_read_b128 v[246:249], v163 offset:49152
	ds_read_b128 v[250:253], v163 offset:53248
	ds_read_b128 v[194:197], v163 offset:57344
	ds_read_b128 v[202:205], v163 offset:61440
	s_waitcnt lgkmcnt(0)
	s_barrier
	s_setprio 1
	v_mfma_f32_32x32x16_bf16 v[48:63], v[64:67], v[76:79], v[48:63]
	v_mfma_f32_32x32x16_bf16 v[32:47], v[64:67], v[80:83], v[32:47]
	v_mfma_f32_32x32x16_bf16 v[16:31], v[64:67], v[84:87], v[16:31]
	v_mfma_f32_32x32x16_bf16 v[0:15], v[64:67], v[88:91], v[0:15]
	v_mfma_f32_32x32x16_bf16 v[48:63], v[92:95], v[96:99], v[48:63]
	v_mfma_f32_32x32x16_bf16 v[32:47], v[92:95], v[100:103], v[32:47]
	v_mfma_f32_32x32x16_bf16 v[16:31], v[92:95], v[104:107], v[16:31]
	v_mfma_f32_32x32x16_bf16 v[0:15], v[92:95], v[108:111], v[0:15]
	v_mfma_f32_32x32x16_bf16 v[48:63], v[112:115], v[222:225], v[48:63]
	v_mfma_f32_32x32x16_bf16 v[32:47], v[112:115], v[230:233], v[32:47]
	v_mfma_f32_32x32x16_bf16 v[16:31], v[112:115], v[234:237], v[16:31]
	v_mfma_f32_32x32x16_bf16 v[0:15], v[112:115], v[238:241], v[0:15]
	v_mfma_f32_32x32x16_bf16 v[48:63], v[242:245], v[246:249], v[48:63]
	v_mfma_f32_32x32x16_bf16 v[32:47], v[242:245], v[250:253], v[32:47]
	v_mfma_f32_32x32x16_bf16 v[16:31], v[242:245], v[194:197], v[16:31]
	v_mfma_f32_32x32x16_bf16 v[0:15], v[242:245], v[202:205], v[0:15]
	s_setprio 0
	s_branch .LBB0_262

.LBB0_266:
	v_add_u32_e32 v164, s76, v173
	v_ashrrev_i32_e32 v165, 31, v164
	v_lshl_add_u64 v[64:65], v[164:165], 2, s[18:19]
	v_add_co_u32_e32 v66, vcc, 0x10000, v64
	v_or_b32_e32 v126, 9, v164
	s_nop 0
	v_addc_co_u32_e32 v67, vcc, 0, v65, vcc
	global_load_dwordx4 v[92:95], v[64:65], off
	global_load_dwordx4 v[96:99], v[66:67], off
	v_add_co_u32_e32 v66, vcc, 0x20000, v64
	v_ashrrev_i32_e32 v127, 31, v126
	s_nop 0
	v_addc_co_u32_e32 v67, vcc, 0, v65, vcc
	v_add_co_u32_e32 v68, vcc, 0x30000, v64
	v_lshl_add_u64 v[126:127], v[126:127], 2, s[18:19]
	s_nop 0
	v_addc_co_u32_e32 v69, vcc, 0, v65, vcc
	global_load_dwordx4 v[100:103], v[66:67], off
	global_load_dwordx4 v[104:107], v[68:69], off
	v_add_co_u32_e32 v66, vcc, 0x40000, v64
	s_lshl_b64 s[80:81], s[80:81], 2
	s_nop 0
	v_addc_co_u32_e32 v67, vcc, 0, v65, vcc
	v_add_co_u32_e32 v68, vcc, 0x50000, v64
	s_add_u32 s80, s84, s80
	s_nop 0
	v_addc_co_u32_e32 v69, vcc, 0, v65, vcc
	global_load_dwordx4 v[108:111], v[66:67], off
	global_load_dwordx4 v[112:115], v[68:69], off
	v_add_co_u32_e32 v66, vcc, 0x60000, v64
	s_addc_u32 s81, s85, s81
	s_nop 0
	v_addc_co_u32_e32 v67, vcc, 0, v65, vcc
	v_add_co_u32_e32 v64, vcc, 0x70000, v64
	global_load_dwordx4 v[116:119], v[66:67], off
	s_nop 0
	v_addc_co_u32_e32 v65, vcc, 0, v65, vcc
	global_load_dwordx4 v[120:123], v[64:65], off
	v_or_b32_e32 v64, 8, v164
	v_ashrrev_i32_e32 v65, 31, v64
	v_lshl_add_u64 v[88:89], v[64:65], 2, s[18:19]
	v_add_co_u32_e32 v64, vcc, s86, v88
	s_cmp_gt_i32 s95, 23
	s_nop 0
	v_addc_co_u32_e32 v65, vcc, 0, v89, vcc
	v_add_co_u32_e32 v68, vcc, s87, v88
	global_load_dword v124, v[88:89], off
	s_nop 0
	global_load_dwordx4 v[64:67], v[64:65], off
	v_addc_co_u32_e32 v69, vcc, 0, v89, vcc
	v_add_co_u32_e32 v72, vcc, s88, v88
	s_waitcnt vmcnt(0)
	v_mov_b32_e32 v128, v96
	v_addc_co_u32_e32 v73, vcc, 0, v89, vcc
	v_add_co_u32_e32 v76, vcc, s89, v88
	global_load_dwordx4 v[68:71], v[68:69], off
	s_nop 0
	global_load_dwordx4 v[72:75], v[72:73], off
	v_addc_co_u32_e32 v77, vcc, 0, v89, vcc
	v_add_co_u32_e32 v80, vcc, s90, v88
	v_mov_b32_e32 v130, v104
	s_nop 0
	v_addc_co_u32_e32 v81, vcc, 0, v89, vcc
	v_add_co_u32_e32 v84, vcc, s91, v88
	global_load_dwordx4 v[76:79], v[76:77], off
	s_nop 0
	global_load_dwordx4 v[80:83], v[80:81], off
	v_addc_co_u32_e32 v85, vcc, 0, v89, vcc
	v_add_co_u32_e32 v88, vcc, s92, v88
	global_load_dwordx4 v[84:87], v[84:85], off
	s_nop 0
	v_addc_co_u32_e32 v89, vcc, 0, v89, vcc
	global_load_dwordx4 v[88:91], v[88:89], off
	v_mov_b32_e32 v129, v112
	global_load_dwordx3 v[148:150], v[126:127], off
	v_mov_b32_e32 v126, v92
	v_mov_b32_e32 v127, v108
	v_pk_add_f32 v[126:127], v[126:127], v[128:129]
	v_mov_b32_e32 v129, v116
	v_mov_b32_e32 v108, v93
	v_mov_b32_e32 v112, v97
	v_mov_b32_e32 v131, v120
	v_mov_b32_e32 v116, v101
	v_mov_b32_e32 v120, v105
	v_pk_add_f32 v[92:93], v[108:109], v[112:113]
	v_pk_add_f32 v[96:97], v[116:117], v[120:121]
	v_mov_b32_e32 v128, v100
	v_pk_add_f32 v[92:93], v[92:93], v[96:97]
	v_mov_b32_e32 v96, v98
	v_add_f32_e32 v215, v92, v93
	v_mov_b32_e32 v92, v94
	v_mov_b32_e32 v93, v110
	v_mov_b32_e32 v97, v114
	v_pk_add_f32 v[92:93], v[92:93], v[96:97]
	v_mov_b32_e32 v96, v102
	v_mov_b32_e32 v97, v118
	v_mov_b32_e32 v100, v106
	v_mov_b32_e32 v101, v122
	v_pk_add_f32 v[96:97], v[96:97], v[100:101]
	v_mov_b32_e32 v110, v95
	v_pk_add_f32 v[92:93], v[92:93], v[96:97]
	v_mov_b32_e32 v114, v99
	v_mov_b32_e32 v118, v103
	v_mov_b32_e32 v122, v107
	v_add_f32_e32 v216, v92, v93
	v_pk_add_f32 v[92:93], v[110:111], v[114:115]
	v_pk_add_f32 v[94:95], v[118:119], v[122:123]
	v_pk_add_f32 v[128:129], v[128:129], v[130:131]
	v_pk_add_f32 v[92:93], v[92:93], v[94:95]
	v_pk_add_f32 v[126:127], v[126:127], v[128:129]
	v_add_f32_e32 v217, v92, v93
	v_mov_b32_e32 v92, v64
	v_add_f32_e32 v165, v126, v127
	s_waitcnt vmcnt(6)
	v_mov_b32_e32 v94, v68
	s_waitcnt vmcnt(5)
	v_mov_b32_e32 v96, v72
	s_waitcnt vmcnt(4)
	v_mov_b32_e32 v125, v76
	s_waitcnt vmcnt(3)
	v_mov_b32_e32 v93, v80
	v_pk_add_f32 v[92:93], v[124:125], v[92:93]
	v_mov_b32_e32 v80, v65
	s_waitcnt vmcnt(2)
	v_mov_b32_e32 v95, v84
	v_mov_b32_e32 v84, v69
	s_waitcnt vmcnt(1)
	v_mov_b32_e32 v97, v88
	v_pk_add_f32 v[94:95], v[94:95], v[96:97]
	s_waitcnt vmcnt(0)
	v_mov_b32_e32 v76, v148
	v_pk_add_f32 v[92:93], v[92:93], v[94:95]
	v_pk_add_f32 v[76:77], v[76:77], v[80:81]
	v_add_f32_e32 v72, v92, v93
	v_or_b32_e32 v92, 16, v164
	v_ashrrev_i32_e32 v93, 31, v92
	v_lshl_add_u64 v[92:93], v[92:93], 2, s[18:19]
	v_add_co_u32_e32 v80, vcc, s86, v92
	global_load_dword v64, v[92:93], off
	s_nop 0
	v_addc_co_u32_e32 v81, vcc, 0, v93, vcc
	v_add_co_u32_e32 v94, vcc, s87, v92
	v_mov_b32_e32 v88, v73
	s_nop 0
	v_addc_co_u32_e32 v95, vcc, 0, v93, vcc
	global_load_dwordx4 v[132:135], v[80:81], off
	global_load_dwordx4 v[136:139], v[94:95], off
	v_add_co_u32_e32 v80, vcc, s88, v92
	v_pk_add_f32 v[68:69], v[84:85], v[88:89]
	s_nop 0
	v_addc_co_u32_e32 v81, vcc, 0, v93, vcc
	v_add_co_u32_e32 v94, vcc, s89, v92
	v_pk_add_f32 v[76:77], v[76:77], v[68:69]
	s_nop 0
	v_addc_co_u32_e32 v95, vcc, 0, v93, vcc
	global_load_dwordx4 v[104:107], v[80:81], off
	global_load_dwordx4 v[140:143], v[94:95], off
	v_add_co_u32_e32 v80, vcc, s90, v92
	v_or_b32_e32 v68, 24, v164
	s_nop 0
	v_addc_co_u32_e32 v81, vcc, 0, v93, vcc
	v_add_co_u32_e32 v94, vcc, s91, v92
	v_ashrrev_i32_e32 v69, 31, v68
	s_nop 0
	v_addc_co_u32_e32 v95, vcc, 0, v93, vcc
	global_load_dwordx4 v[144:147], v[80:81], off
	global_load_dwordx4 v[116:119], v[94:95], off
	v_add_co_u32_e32 v80, vcc, s92, v92
	v_add_f32_e32 v73, v76, v77
	s_nop 0
	v_addc_co_u32_e32 v81, vcc, 0, v93, vcc
	global_load_dwordx4 v[120:123], v[80:81], off
	v_or_b32_e32 v80, 17, v164
	v_ashrrev_i32_e32 v81, 31, v80
	v_lshl_add_u64 v[80:81], v[80:81], 2, s[18:19]
	global_load_dwordx3 v[218:220], v[80:81], off
	v_lshl_add_u64 v[80:81], v[68:69], 2, s[18:19]
	v_add_co_u32_e32 v84, vcc, s86, v80
	v_or_b32_e32 v76, 25, v164
	s_nop 0
	v_addc_co_u32_e32 v85, vcc, 0, v81, vcc
	global_load_dword v68, v[80:81], off
	global_load_dwordx4 v[92:95], v[84:85], off
	v_add_co_u32_e32 v84, vcc, s87, v80
	v_ashrrev_i32_e32 v77, 31, v76
	s_nop 0
	v_addc_co_u32_e32 v85, vcc, 0, v81, vcc
	v_add_co_u32_e32 v88, vcc, s88, v80
	v_lshl_add_u64 v[76:77], v[76:77], 2, s[18:19]
	s_nop 0
	v_addc_co_u32_e32 v89, vcc, 0, v81, vcc
	global_load_dwordx4 v[96:99], v[84:85], off
	global_load_dwordx4 v[100:103], v[88:89], off
	v_add_co_u32_e32 v84, vcc, s89, v80
	s_waitcnt vmcnt(8)
	v_mov_b32_e32 v65, v140
	v_addc_co_u32_e32 v85, vcc, 0, v81, vcc
	v_add_co_u32_e32 v88, vcc, s90, v80
	s_waitcnt vmcnt(4)
	v_mov_b32_e32 v140, v218
	v_addc_co_u32_e32 v89, vcc, 0, v81, vcc
	global_load_dwordx4 v[108:111], v[84:85], off
	global_load_dwordx4 v[112:115], v[88:89], off
	v_add_co_u32_e32 v84, vcc, s91, v80
	global_load_dwordx3 v[152:154], v[76:77], off
	s_nop 0
	v_addc_co_u32_e32 v85, vcc, 0, v81, vcc
	v_add_co_u32_e32 v80, vcc, s92, v80
	global_load_dwordx4 v[124:127], v[84:85], off
	s_nop 0
	v_addc_co_u32_e32 v81, vcc, 0, v81, vcc
	global_load_dwordx4 v[128:131], v[80:81], off
	v_mov_b32_e32 v76, v149
	v_mov_b32_e32 v77, v78
	v_mov_b32_e32 v80, v66
	v_mov_b32_e32 v81, v82
	v_pk_add_f32 v[76:77], v[76:77], v[80:81]
	v_mov_b32_e32 v81, v86
	v_mov_b32_e32 v85, v90
	v_mov_b32_e32 v78, v150
	v_mov_b32_e32 v82, v67
	v_mov_b32_e32 v86, v71
	v_mov_b32_e32 v90, v75
	v_mov_b32_e32 v80, v70
	v_pk_add_f32 v[66:67], v[78:79], v[82:83]
	v_pk_add_f32 v[70:71], v[86:87], v[90:91]
	v_mov_b32_e32 v84, v74
	v_pk_add_f32 v[66:67], v[66:67], v[70:71]
	v_mov_b32_e32 v70, v104
	v_add_f32_e32 v75, v66, v67
	v_mov_b32_e32 v66, v132
	v_mov_b32_e32 v67, v144
	v_pk_add_f32 v[64:65], v[64:65], v[66:67]
	v_mov_b32_e32 v66, v136
	v_mov_b32_e32 v67, v116
	v_mov_b32_e32 v71, v120
	v_pk_add_f32 v[66:67], v[66:67], v[70:71]
	v_mov_b32_e32 v144, v133
	v_pk_add_f32 v[64:65], v[64:65], v[66:67]
	v_mov_b32_e32 v116, v137
	v_mov_b32_e32 v120, v105
	v_add_f32_e32 v78, v64, v65
	v_pk_add_f32 v[64:65], v[140:141], v[144:145]
	v_pk_add_f32 v[66:67], v[116:117], v[120:121]
	v_pk_add_f32 v[80:81], v[80:81], v[84:85]
	v_pk_add_f32 v[64:65], v[64:65], v[66:67]
	v_mov_b32_e32 v66, v134
	v_add_f32_e32 v79, v64, v65
	v_mov_b32_e32 v64, v219
	v_mov_b32_e32 v65, v142
	v_mov_b32_e32 v67, v146
	v_pk_add_f32 v[76:77], v[76:77], v[80:81]
	v_pk_add_f32 v[64:65], v[64:65], v[66:67]
	v_mov_b32_e32 v66, v138
	v_mov_b32_e32 v67, v118
	v_mov_b32_e32 v70, v106
	v_mov_b32_e32 v71, v122
	v_add_f32_e32 v74, v76, v77
	v_pk_add_f32 v[66:67], v[66:67], v[70:71]
	v_or_b32_e32 v76, s78, v156
	v_pk_add_f32 v[64:65], v[64:65], v[66:67]
	v_ashrrev_i32_e32 v77, 31, v76
	v_add_f32_e32 v85, v64, v65
	v_lshl_add_u64 v[64:65], v[76:77], 2, s[80:81]
	global_load_dword v81, v[64:65], off
	global_load_dword v80, v[64:65], off offset:128
	global_load_dword v82, v[64:65], off offset:256
	global_load_dword v83, v[64:65], off offset:384
	v_mov_b32_e32 v142, v220
	v_mov_b32_e32 v146, v135
	v_mov_b32_e32 v118, v139
	v_mov_b32_e32 v122, v107
	v_pk_add_f32 v[66:67], v[142:143], v[146:147]
	v_pk_add_f32 v[70:71], v[118:119], v[122:123]
	v_fmamk_f32 v64, v73, 0x3a800000, v209
	v_pk_add_f32 v[66:67], v[66:67], v[70:71]
	s_waitcnt vmcnt(9)
	v_mov_b32_e32 v70, v100
	v_add_f32_e32 v87, v66, v67
	v_mov_b32_e32 v66, v92
	v_mov_b32_e32 v65, v48
	s_waitcnt vmcnt(8)
	v_mov_b32_e32 v69, v108
	s_waitcnt vmcnt(7)
	v_mov_b32_e32 v67, v112
	v_pk_add_f32 v[66:67], v[68:69], v[66:67]
	v_mov_b32_e32 v68, v96
	s_waitcnt vmcnt(6)
	v_mov_b32_e32 v108, v152
	v_mov_b32_e32 v112, v93
	v_mov_b32_e32 v48, v33
	v_mov_b32_e32 v33, v50
	v_mov_b32_e32 v50, v35
	s_waitcnt vmcnt(5)
	v_mov_b32_e32 v69, v124
	v_mov_b32_e32 v124, v97
	s_mov_b64 s[80:81], -1
	s_waitcnt vmcnt(4)
	v_mov_b32_e32 v71, v128
	v_pk_add_f32 v[68:69], v[68:69], v[70:71]
	v_mov_b32_e32 v128, v101
	v_pk_add_f32 v[66:67], v[66:67], v[68:69]
	v_pk_add_f32 v[68:69], v[124:125], v[128:129]
	v_add_f32_e32 v89, v66, v67
	v_pk_add_f32 v[66:67], v[108:109], v[112:113]
	v_mov_b32_e32 v70, v102
	v_pk_add_f32 v[66:67], v[66:67], v[68:69]
	v_mov_b32_e32 v68, v94
	v_add_f32_e32 v91, v66, v67
	v_mov_b32_e32 v66, v153
	v_mov_b32_e32 v67, v110
	v_mov_b32_e32 v69, v114
	v_pk_add_f32 v[66:67], v[66:67], v[68:69]
	v_mov_b32_e32 v68, v98
	v_mov_b32_e32 v69, v126
	v_mov_b32_e32 v71, v130
	v_pk_add_f32 v[68:69], v[68:69], v[70:71]
	v_mov_b32_e32 v110, v154
	v_pk_add_f32 v[66:67], v[66:67], v[68:69]
	v_mov_b32_e32 v114, v95
	v_mov_b32_e32 v126, v99
	v_mov_b32_e32 v130, v103
	v_rsq_f32_e32 v94, v64
	v_fmamk_f32 v64, v74, 0x3a800000, v209
	v_add_f32_e32 v70, v66, v67
	v_pk_add_f32 v[66:67], v[110:111], v[114:115]
	v_pk_add_f32 v[68:69], v[126:127], v[130:131]
	v_rsq_f32_e32 v96, v64
	v_fmamk_f32 v64, v75, 0x3a800000, v209
	v_pk_add_f32 v[66:67], v[66:67], v[68:69]
	v_rsq_f32_e32 v98, v64
	v_fmamk_f32 v64, v78, 0x3a800000, v209
	v_add_f32_e32 v66, v66, v67
	v_fmamk_f32 v67, v165, 0x3a800000, v209
	v_rsq_f32_e32 v100, v64
	v_fmamk_f32 v64, v79, 0x3a800000, v209
	v_rsq_f32_e32 v84, v67
	v_fmamk_f32 v67, v215, 0x3a800000, v209
	v_rsq_f32_e32 v102, v64
	v_fmamk_f32 v64, v85, 0x3a800000, v209
	v_rsq_f32_e32 v86, v67
	v_fmamk_f32 v67, v216, 0x3a800000, v209
	v_rsq_f32_e32 v104, v64
	v_fmamk_f32 v64, v87, 0x3a800000, v209
	v_rsq_f32_e32 v88, v67
	v_fmamk_f32 v67, v217, 0x3a800000, v209
	v_rsq_f32_e32 v106, v64
	v_fmamk_f32 v64, v89, 0x3a800000, v209
	v_rsq_f32_e32 v90, v67
	v_fmamk_f32 v67, v72, 0x3a800000, v209
	v_rsq_f32_e32 v108, v64
	v_fmamk_f32 v64, v91, 0x3a800000, v209
	v_rsq_f32_e32 v92, v67
	v_rsq_f32_e32 v110, v64
	v_fmamk_f32 v64, v70, 0x3a800000, v209
	v_rsq_f32_e32 v112, v64
	v_fmamk_f32 v64, v66, 0x3a800000, v209
	v_rsq_f32_e32 v114, v64
	v_mov_b32_e32 v64, v32
	v_mov_b32_e32 v32, v34
	s_waitcnt vmcnt(2)
	v_pk_fma_f32 v[72:73], v[32:33], v[88:89], v[80:81] op_sel_hi:[1,0,1]
	v_mov_b32_e32 v32, v36
	v_mov_b32_e32 v33, v52
	v_pk_fma_f32 v[68:69], v[32:33], v[92:93], v[80:81] op_sel_hi:[1,0,1]
	v_mov_b32_e32 v32, v38
	v_mov_b32_e32 v33, v54
	v_pk_fma_f32 v[78:79], v[64:65], v[84:85], v[80:81] op_sel_hi:[1,0,1]
	v_mov_b32_e32 v52, v37
	v_pk_fma_f32 v[64:65], v[32:33], v[96:97], v[80:81] op_sel_hi:[1,0,1]
	v_mov_b32_e32 v32, v40
	v_mov_b32_e32 v33, v56
	v_pk_fma_f32 v[66:67], v[52:53], v[94:95], v[80:81] op_sel_hi:[1,0,1]
	v_pk_fma_f32 v[52:53], v[32:33], v[100:101], v[80:81] op_sel_hi:[1,0,1]
	v_mov_b32_e32 v32, v42
	v_mov_b32_e32 v33, v58
	v_pk_fma_f32 v[74:75], v[48:49], v[86:87], v[80:81] op_sel_hi:[1,0,1]
	v_pk_fma_f32 v[48:49], v[32:33], v[104:105], v[80:81] op_sel_hi:[1,0,1]
	v_mov_b32_e32 v32, v44
	v_mov_b32_e32 v33, v60
	v_mov_b32_e32 v54, v39
	v_mov_b32_e32 v56, v41
	v_mov_b32_e32 v58, v43
	v_pk_fma_f32 v[38:39], v[32:33], v[108:109], v[80:81] op_sel_hi:[1,0,1]
	v_mov_b32_e32 v60, v45
	v_mov_b32_e32 v32, v46
	v_mov_b32_e32 v33, v62
	v_mov_b32_e32 v62, v47
	v_pk_fma_f32 v[70:71], v[50:51], v[90:91], v[80:81] op_sel_hi:[1,0,1]
	v_pk_fma_f32 v[54:55], v[54:55], v[98:99], v[80:81] op_sel_hi:[1,0,1]
	v_pk_fma_f32 v[50:51], v[56:57], v[102:103], v[80:81] op_sel_hi:[1,0,1]
	v_pk_fma_f32 v[40:41], v[58:59], v[106:107], v[80:81] op_sel_hi:[1,0,1]
	v_pk_fma_f32 v[36:37], v[60:61], v[110:111], v[80:81] op_sel_hi:[1,0,1]
	v_pk_fma_f32 v[34:35], v[32:33], v[112:113], v[80:81] op_sel_hi:[1,0,1]
	v_pk_fma_f32 v[32:33], v[62:63], v[114:115], v[80:81] op_sel_hi:[1,0,1]
	s_waitcnt vmcnt(1)
	v_fma_f32 v57, v16, v84, v82
	v_fma_f32 v47, v17, v86, v82
	v_fma_f32 v46, v18, v88, v82
	v_fma_f32 v45, v19, v90, v82
	v_fma_f32 v44, v20, v92, v82
	v_fma_f32 v43, v21, v94, v82
	v_fma_f32 v42, v22, v96, v82
	v_fma_f32 v23, v23, v98, v82
	v_fma_f32 v22, v24, v100, v82
	v_fma_f32 v21, v25, v102, v82
	v_fma_f32 v20, v26, v104, v82
	v_fma_f32 v19, v27, v106, v82
	v_fma_f32 v18, v28, v108, v82
	v_fma_f32 v17, v29, v110, v82
	v_fma_f32 v16, v30, v112, v82
	v_fmac_f32_e32 v82, v31, v114
	s_waitcnt vmcnt(0)
	v_fma_f32 v56, v0, v84, v83
	v_fma_f32 v31, v1, v86, v83
	v_fma_f32 v30, v2, v88, v83
	v_fma_f32 v29, v3, v90, v83
	v_fma_f32 v28, v4, v92, v83
	v_fma_f32 v27, v5, v94, v83
	v_fma_f32 v26, v6, v96, v83
	v_fma_f32 v25, v7, v98, v83
	v_fma_f32 v24, v8, v100, v83
	v_fma_f32 v9, v9, v102, v83
	v_fma_f32 v8, v10, v104, v83
	v_fma_f32 v7, v11, v106, v83
	v_fma_f32 v6, v12, v108, v83
	v_fma_f32 v5, v13, v110, v83
	v_fma_f32 v4, v14, v112, v83
	v_fmac_f32_e32 v83, v15, v114
	s_cbranch_scc0 .LBB0_496
	v_cndmask_b32_e64 v0, 0, 1, s[4:5]
	s_cmp_gt_u32 s10, 4
	v_cmp_ne_u32_e64 s[4:5], 1, v0
	s_cbranch_scc0 .LBB0_333
	v_mov_b32_e32 v0, s93
	ds_read_b64 v[0:1], v0
	v_and_b32_e32 v11, 64, v214
	v_xor_b32_e32 v10, 1, v214
	v_add_u32_e32 v13, 64, v11
	v_pk_mul_f32 v[2:3], v[78:79], v[78:79]
	s_waitcnt lgkmcnt(0)
	v_readfirstlane_b32 s80, v0
	v_readfirstlane_b32 s81, v1
	s_nop 4
	global_load_dword v1, v210, s[80:81] offset:1280
	global_load_dword v0, v210, s[80:81] offset:1408
	v_cmp_lt_i32_e32 vcc, v10, v13
	v_add_f32_e32 v2, v3, v2
	v_xor_b32_e32 v11, 4, v214
	v_cndmask_b32_e32 v3, v214, v10, vcc
	v_lshlrev_b32_e32 v14, 2, v3
	ds_bpermute_b32 v3, v14, v2
	v_xor_b32_e32 v10, 2, v214
	v_cmp_lt_i32_e32 vcc, v10, v13
	v_xor_b32_e32 v12, 8, v214
	v_xor_b32_e32 v15, 16, v214
	v_cndmask_b32_e32 v10, v214, v10, vcc
	v_lshlrev_b32_e32 v10, 2, v10
	s_waitcnt lgkmcnt(0)
	v_add_f32_e32 v2, v2, v3
	ds_bpermute_b32 v3, v10, v2
	v_cmp_lt_i32_e32 vcc, v11, v13
	s_mov_b64 s[80:81], -1
	s_waitcnt lgkmcnt(0)
	v_add_f32_e32 v2, v2, v3
	v_cndmask_b32_e32 v11, v214, v11, vcc
	v_lshlrev_b32_e32 v11, 2, v11
	ds_bpermute_b32 v3, v11, v2
	v_cmp_lt_i32_e32 vcc, v12, v13
	s_waitcnt lgkmcnt(0)
	v_add_f32_e32 v2, v2, v3
	v_cndmask_b32_e32 v12, v214, v12, vcc
	v_lshlrev_b32_e32 v12, 2, v12
	ds_bpermute_b32 v3, v12, v2
	v_cmp_lt_i32_e32 vcc, v15, v13
	s_waitcnt lgkmcnt(0)
	v_add_f32_e32 v2, v2, v3
	v_cndmask_b32_e32 v13, v214, v15, vcc
	v_lshlrev_b32_e32 v13, 2, v13
	ds_bpermute_b32 v3, v13, v2
	s_and_b64 vcc, exec, s[4:5]
	s_waitcnt lgkmcnt(0)
	v_add_f32_e32 v2, v2, v3
	v_fmamk_f32 v2, v2, 0x3c800000, v209
	v_rsq_f32_e32 v2, v2
	s_waitcnt vmcnt(0)
	v_pk_mul_f32 v[2:3], v[0:1], v[2:3] op_sel_hi:[1,0]
	s_nop 0
	v_pk_mul_f32 v[2:3], v[78:79], v[2:3]
	s_cbranch_vccnz .LBB0_270
	v_lshl_or_b32 v58, v164, 6, v156
	v_ashrrev_i32_e32 v59, 31, v58
	v_lshl_add_u64 v[58:59], v[58:59], 2, s[24:25]
	s_mov_b64 s[80:81], 0
	global_store_dword v[58:59], v3, off sc1
	global_store_dword v[58:59], v2, off offset:128 sc1

.LBB0_272:
	v_cvt_pk_bf16_f32 v60, v2, s0
	v_add_u32_e32 v2, s11, v173
	v_mul_lo_u32 v61, v2, s94
	v_or_b32_e32 v2, v61, v174
	v_cvt_pk_bf16_f32 v15, v3, s0
	v_ashrrev_i32_e32 v3, 31, v2
	v_lshl_add_u64 v[2:3], v[2:3], 1, s[22:23]
	global_store_short v[2:3], v15, off sc1
	v_or_b32_e32 v2, v61, v175
	v_ashrrev_i32_e32 v3, 31, v2
	v_lshl_add_u64 v[2:3], v[2:3], 1, s[22:23]
	v_or_b32_e32 v58, 0xc0, v61
	global_store_short v[2:3], v60, off sc1
	v_add_u32_e32 v2, v58, v174
	v_ashrrev_i32_e32 v3, 31, v2
	v_lshl_add_u64 v[2:3], v[2:3], 1, s[22:23]
	global_store_short v[2:3], v15, off sc1
	v_add_u32_e32 v2, v58, v175
	v_ashrrev_i32_e32 v3, 31, v2
	v_lshl_add_u64 v[2:3], v[2:3], 1, s[22:23]
	v_or_b32_e32 v58, 0x180, v61
	global_store_short v[2:3], v60, off sc1
	v_add_u32_e32 v2, v58, v174
	v_ashrrev_i32_e32 v3, 31, v2
	v_lshl_add_u64 v[2:3], v[2:3], 1, s[22:23]
	global_store_short v[2:3], v15, off sc1
	v_add_u32_e32 v2, v58, v175
	v_ashrrev_i32_e32 v3, 31, v2
	v_lshl_add_u64 v[2:3], v[2:3], 1, s[22:23]
	v_add_u32_e32 v58, 0x240, v61
	global_store_short v[2:3], v60, off sc1
	v_or_b32_e32 v2, v58, v174
	v_ashrrev_i32_e32 v3, 31, v2
	v_lshl_add_u64 v[2:3], v[2:3], 1, s[22:23]
	global_store_short v[2:3], v15, off sc1
	v_or_b32_e32 v2, v58, v175
	v_ashrrev_i32_e32 v3, 31, v2
	v_lshl_add_u64 v[2:3], v[2:3], 1, s[22:23]
	v_add_u32_e32 v58, 0x300, v61
	global_store_short v[2:3], v60, off sc1
	v_or_b32_e32 v2, v58, v174
	v_ashrrev_i32_e32 v3, 31, v2
	v_lshl_add_u64 v[2:3], v[2:3], 1, s[22:23]
	global_store_short v[2:3], v15, off sc1
	v_or_b32_e32 v2, v58, v175
	v_pk_mul_f32 v[58:59], v[74:75], v[74:75]
	v_ashrrev_i32_e32 v3, 31, v2
	v_add_f32_e32 v58, v59, v58
	ds_bpermute_b32 v59, v14, v58
	v_lshl_add_u64 v[2:3], v[2:3], 1, s[22:23]
	v_add_u32_e32 v62, 0x3c0, v61
	global_store_short v[2:3], v60, off sc1
	v_add_u32_e32 v2, v62, v174
	s_waitcnt lgkmcnt(0)
	v_add_f32_e32 v58, v58, v59
	ds_bpermute_b32 v59, v10, v58
	v_ashrrev_i32_e32 v3, 31, v2
	v_lshl_add_u64 v[2:3], v[2:3], 1, s[22:23]
	global_store_short v[2:3], v15, off sc1
	v_add_u32_e32 v2, v62, v175
	s_waitcnt lgkmcnt(0)
	v_add_f32_e32 v58, v58, v59
	ds_bpermute_b32 v59, v11, v58
	v_ashrrev_i32_e32 v3, 31, v2
	v_lshl_add_u64 v[2:3], v[2:3], 1, s[22:23]
	v_add_u32_e32 v62, 0x480, v61
	global_store_short v[2:3], v60, off sc1
	s_waitcnt lgkmcnt(0)
	v_add_f32_e32 v58, v58, v59
	ds_bpermute_b32 v59, v12, v58
	v_add_u32_e32 v2, v62, v174
	v_ashrrev_i32_e32 v3, 31, v2
	v_lshl_add_u64 v[2:3], v[2:3], 1, s[22:23]
	global_store_short v[2:3], v15, off sc1
	v_add_u32_e32 v2, v62, v175
	s_waitcnt lgkmcnt(0)
	v_add_f32_e32 v58, v58, v59
	v_ashrrev_i32_e32 v3, 31, v2
	ds_bpermute_b32 v59, v13, v58
	v_lshl_add_u64 v[2:3], v[2:3], 1, s[22:23]
	v_add_u32_e32 v61, 0x540, v61
	global_store_short v[2:3], v60, off sc1
	v_or_b32_e32 v2, v61, v174
	v_ashrrev_i32_e32 v3, 31, v2
	v_lshl_add_u64 v[2:3], v[2:3], 1, s[22:23]
	global_store_short v[2:3], v15, off sc1
	s_waitcnt lgkmcnt(0)
	v_add_f32_e32 v3, v58, v59
	v_fmamk_f32 v3, v3, 0x3c800000, v209
	v_rsq_f32_e32 v58, v3
	v_or_b32_e32 v2, v61, v175
	v_ashrrev_i32_e32 v3, 31, v2
	v_lshl_add_u64 v[2:3], v[2:3], 1, s[22:23]
	global_store_short v[2:3], v60, off sc1
	v_pk_mul_f32 v[2:3], v[0:1], v[58:59] op_sel_hi:[1,0]
	s_and_b64 vcc, exec, s[4:5]
	v_pk_mul_f32 v[2:3], v[74:75], v[2:3]
	s_mov_b64 s[80:81], -1
	s_cbranch_vccnz .LBB0_274
	v_add_u32_e32 v15, s76, v176
	v_lshl_or_b32 v58, v15, 6, v156
	v_ashrrev_i32_e32 v59, 31, v58
	v_lshl_add_u64 v[58:59], v[58:59], 2, s[24:25]
	s_mov_b64 s[80:81], 0
	global_store_dword v[58:59], v3, off sc1
	global_store_dword v[58:59], v2, off offset:128 sc1

.LBB0_276:
	v_cvt_pk_bf16_f32 v60, v2, s0
	v_add_u32_e32 v2, s11, v176
	v_mul_lo_u32 v61, v2, s94
	v_or_b32_e32 v2, v61, v174
	v_cvt_pk_bf16_f32 v15, v3, s0
	v_ashrrev_i32_e32 v3, 31, v2
	v_lshl_add_u64 v[2:3], v[2:3], 1, s[22:23]
	global_store_short v[2:3], v15, off sc1
	v_or_b32_e32 v2, v61, v175
	v_ashrrev_i32_e32 v3, 31, v2
	v_lshl_add_u64 v[2:3], v[2:3], 1, s[22:23]
	v_or_b32_e32 v58, 0xc0, v61
	global_store_short v[2:3], v60, off sc1
	v_add_u32_e32 v2, v58, v174
	v_ashrrev_i32_e32 v3, 31, v2
	v_lshl_add_u64 v[2:3], v[2:3], 1, s[22:23]
	global_store_short v[2:3], v15, off sc1
	v_add_u32_e32 v2, v58, v175
	v_ashrrev_i32_e32 v3, 31, v2
	v_lshl_add_u64 v[2:3], v[2:3], 1, s[22:23]
	v_or_b32_e32 v58, 0x180, v61
	global_store_short v[2:3], v60, off sc1
	v_add_u32_e32 v2, v58, v174
	v_ashrrev_i32_e32 v3, 31, v2
	v_lshl_add_u64 v[2:3], v[2:3], 1, s[22:23]
	global_store_short v[2:3], v15, off sc1
	v_add_u32_e32 v2, v58, v175
	v_ashrrev_i32_e32 v3, 31, v2
	v_lshl_add_u64 v[2:3], v[2:3], 1, s[22:23]
	v_add_u32_e32 v58, 0x240, v61
	global_store_short v[2:3], v60, off sc1
	v_or_b32_e32 v2, v58, v174
	v_ashrrev_i32_e32 v3, 31, v2
	v_lshl_add_u64 v[2:3], v[2:3], 1, s[22:23]
	global_store_short v[2:3], v15, off sc1
	v_or_b32_e32 v2, v58, v175
	v_ashrrev_i32_e32 v3, 31, v2
	v_lshl_add_u64 v[2:3], v[2:3], 1, s[22:23]
	v_add_u32_e32 v58, 0x300, v61
	global_store_short v[2:3], v60, off sc1
	v_or_b32_e32 v2, v58, v174
	v_ashrrev_i32_e32 v3, 31, v2
	v_lshl_add_u64 v[2:3], v[2:3], 1, s[22:23]
	global_store_short v[2:3], v15, off sc1
	v_or_b32_e32 v2, v58, v175
	v_pk_mul_f32 v[58:59], v[72:73], v[72:73]
	v_ashrrev_i32_e32 v3, 31, v2
	v_add_f32_e32 v58, v59, v58
	ds_bpermute_b32 v59, v14, v58
	v_lshl_add_u64 v[2:3], v[2:3], 1, s[22:23]
	v_add_u32_e32 v62, 0x3c0, v61
	global_store_short v[2:3], v60, off sc1
	v_add_u32_e32 v2, v62, v174
	s_waitcnt lgkmcnt(0)
	v_add_f32_e32 v58, v58, v59
	ds_bpermute_b32 v59, v10, v58
	v_ashrrev_i32_e32 v3, 31, v2
	v_lshl_add_u64 v[2:3], v[2:3], 1, s[22:23]
	global_store_short v[2:3], v15, off sc1
	v_add_u32_e32 v2, v62, v175
	s_waitcnt lgkmcnt(0)
	v_add_f32_e32 v58, v58, v59
	ds_bpermute_b32 v59, v11, v58
	v_ashrrev_i32_e32 v3, 31, v2
	v_lshl_add_u64 v[2:3], v[2:3], 1, s[22:23]
	v_add_u32_e32 v62, 0x480, v61
	global_store_short v[2:3], v60, off sc1
	s_waitcnt lgkmcnt(0)
	v_add_f32_e32 v58, v58, v59
	ds_bpermute_b32 v59, v12, v58
	v_add_u32_e32 v2, v62, v174
	v_ashrrev_i32_e32 v3, 31, v2
	v_lshl_add_u64 v[2:3], v[2:3], 1, s[22:23]
	global_store_short v[2:3], v15, off sc1
	v_add_u32_e32 v2, v62, v175
	s_waitcnt lgkmcnt(0)
	v_add_f32_e32 v58, v58, v59
	v_ashrrev_i32_e32 v3, 31, v2
	ds_bpermute_b32 v59, v13, v58
	v_lshl_add_u64 v[2:3], v[2:3], 1, s[22:23]
	v_add_u32_e32 v61, 0x540, v61
	global_store_short v[2:3], v60, off sc1
	v_or_b32_e32 v2, v61, v174
	v_ashrrev_i32_e32 v3, 31, v2
	v_lshl_add_u64 v[2:3], v[2:3], 1, s[22:23]
	global_store_short v[2:3], v15, off sc1
	s_waitcnt lgkmcnt(0)
	v_add_f32_e32 v3, v58, v59
	v_fmamk_f32 v3, v3, 0x3c800000, v209
	v_rsq_f32_e32 v58, v3
	v_or_b32_e32 v2, v61, v175
	v_ashrrev_i32_e32 v3, 31, v2
	v_lshl_add_u64 v[2:3], v[2:3], 1, s[22:23]
	global_store_short v[2:3], v60, off sc1
	v_pk_mul_f32 v[2:3], v[0:1], v[58:59] op_sel_hi:[1,0]
	s_and_b64 vcc, exec, s[4:5]
	v_pk_mul_f32 v[2:3], v[72:73], v[2:3]
	s_mov_b64 s[80:81], -1
	s_cbranch_vccnz .LBB0_278
	v_add_u32_e32 v15, s76, v177
	v_lshl_or_b32 v58, v15, 6, v156
	v_ashrrev_i32_e32 v59, 31, v58
	v_lshl_add_u64 v[58:59], v[58:59], 2, s[24:25]
	s_mov_b64 s[80:81], 0
	global_store_dword v[58:59], v3, off sc1
	global_store_dword v[58:59], v2, off offset:128 sc1

.LBB0_280:
	v_cvt_pk_bf16_f32 v60, v2, s0
	v_add_u32_e32 v2, s11, v177
	v_mul_lo_u32 v61, v2, s94
	v_or_b32_e32 v2, v61, v174
	v_cvt_pk_bf16_f32 v15, v3, s0
	v_ashrrev_i32_e32 v3, 31, v2
	v_lshl_add_u64 v[2:3], v[2:3], 1, s[22:23]
	global_store_short v[2:3], v15, off sc1
	v_or_b32_e32 v2, v61, v175
	v_ashrrev_i32_e32 v3, 31, v2
	v_lshl_add_u64 v[2:3], v[2:3], 1, s[22:23]
	v_or_b32_e32 v58, 0xc0, v61
	global_store_short v[2:3], v60, off sc1
	v_add_u32_e32 v2, v58, v174
	v_ashrrev_i32_e32 v3, 31, v2
	v_lshl_add_u64 v[2:3], v[2:3], 1, s[22:23]
	global_store_short v[2:3], v15, off sc1
	v_add_u32_e32 v2, v58, v175
	v_ashrrev_i32_e32 v3, 31, v2
	v_lshl_add_u64 v[2:3], v[2:3], 1, s[22:23]
	v_or_b32_e32 v58, 0x180, v61
	global_store_short v[2:3], v60, off sc1
	v_add_u32_e32 v2, v58, v174
	v_ashrrev_i32_e32 v3, 31, v2
	v_lshl_add_u64 v[2:3], v[2:3], 1, s[22:23]
	global_store_short v[2:3], v15, off sc1
	v_add_u32_e32 v2, v58, v175
	v_ashrrev_i32_e32 v3, 31, v2
	v_lshl_add_u64 v[2:3], v[2:3], 1, s[22:23]
	v_add_u32_e32 v58, 0x240, v61
	global_store_short v[2:3], v60, off sc1
	v_or_b32_e32 v2, v58, v174
	v_ashrrev_i32_e32 v3, 31, v2
	v_lshl_add_u64 v[2:3], v[2:3], 1, s[22:23]
	global_store_short v[2:3], v15, off sc1
	v_or_b32_e32 v2, v58, v175
	v_ashrrev_i32_e32 v3, 31, v2
	v_lshl_add_u64 v[2:3], v[2:3], 1, s[22:23]
	v_add_u32_e32 v58, 0x300, v61
	global_store_short v[2:3], v60, off sc1
	v_or_b32_e32 v2, v58, v174
	v_ashrrev_i32_e32 v3, 31, v2
	v_lshl_add_u64 v[2:3], v[2:3], 1, s[22:23]
	global_store_short v[2:3], v15, off sc1
	v_or_b32_e32 v2, v58, v175
	v_pk_mul_f32 v[58:59], v[70:71], v[70:71]
	v_ashrrev_i32_e32 v3, 31, v2
	v_add_f32_e32 v58, v59, v58
	ds_bpermute_b32 v59, v14, v58
	v_lshl_add_u64 v[2:3], v[2:3], 1, s[22:23]
	v_add_u32_e32 v62, 0x3c0, v61
	global_store_short v[2:3], v60, off sc1
	v_add_u32_e32 v2, v62, v174
	s_waitcnt lgkmcnt(0)
	v_add_f32_e32 v58, v58, v59
	ds_bpermute_b32 v59, v10, v58
	v_ashrrev_i32_e32 v3, 31, v2
	v_lshl_add_u64 v[2:3], v[2:3], 1, s[22:23]
	global_store_short v[2:3], v15, off sc1
	v_add_u32_e32 v2, v62, v175
	s_waitcnt lgkmcnt(0)
	v_add_f32_e32 v58, v58, v59
	ds_bpermute_b32 v59, v11, v58
	v_ashrrev_i32_e32 v3, 31, v2
	v_lshl_add_u64 v[2:3], v[2:3], 1, s[22:23]
	v_add_u32_e32 v62, 0x480, v61
	global_store_short v[2:3], v60, off sc1
	s_waitcnt lgkmcnt(0)
	v_add_f32_e32 v58, v58, v59
	ds_bpermute_b32 v59, v12, v58
	v_add_u32_e32 v2, v62, v174
	v_ashrrev_i32_e32 v3, 31, v2
	v_lshl_add_u64 v[2:3], v[2:3], 1, s[22:23]
	global_store_short v[2:3], v15, off sc1
	v_add_u32_e32 v2, v62, v175
	s_waitcnt lgkmcnt(0)
	v_add_f32_e32 v58, v58, v59
	v_ashrrev_i32_e32 v3, 31, v2
	ds_bpermute_b32 v59, v13, v58
	v_lshl_add_u64 v[2:3], v[2:3], 1, s[22:23]
	v_add_u32_e32 v61, 0x540, v61
	global_store_short v[2:3], v60, off sc1
	v_or_b32_e32 v2, v61, v174
	v_ashrrev_i32_e32 v3, 31, v2
	v_lshl_add_u64 v[2:3], v[2:3], 1, s[22:23]
	global_store_short v[2:3], v15, off sc1
	s_waitcnt lgkmcnt(0)
	v_add_f32_e32 v3, v58, v59
	v_fmamk_f32 v3, v3, 0x3c800000, v209
	v_rsq_f32_e32 v58, v3
	v_or_b32_e32 v2, v61, v175
	v_ashrrev_i32_e32 v3, 31, v2
	v_lshl_add_u64 v[2:3], v[2:3], 1, s[22:23]
	global_store_short v[2:3], v60, off sc1
	v_pk_mul_f32 v[2:3], v[0:1], v[58:59] op_sel_hi:[1,0]
	s_and_b64 vcc, exec, s[4:5]
	v_pk_mul_f32 v[2:3], v[70:71], v[2:3]
	s_mov_b64 s[80:81], -1
	s_cbranch_vccnz .LBB0_282
	v_add_u32_e32 v15, s76, v178
	v_lshl_or_b32 v58, v15, 6, v156
	v_ashrrev_i32_e32 v59, 31, v58
	v_lshl_add_u64 v[58:59], v[58:59], 2, s[24:25]
	s_mov_b64 s[80:81], 0
	global_store_dword v[58:59], v3, off sc1
	global_store_dword v[58:59], v2, off offset:128 sc1

.LBB0_284:
	v_cvt_pk_bf16_f32 v60, v2, s0
	v_add_u32_e32 v2, s11, v178
	v_mul_lo_u32 v61, v2, s94
	v_or_b32_e32 v2, v61, v174
	v_cvt_pk_bf16_f32 v15, v3, s0
	v_ashrrev_i32_e32 v3, 31, v2
	v_lshl_add_u64 v[2:3], v[2:3], 1, s[22:23]
	global_store_short v[2:3], v15, off sc1
	v_or_b32_e32 v2, v61, v175
	v_ashrrev_i32_e32 v3, 31, v2
	v_lshl_add_u64 v[2:3], v[2:3], 1, s[22:23]
	v_or_b32_e32 v58, 0xc0, v61
	global_store_short v[2:3], v60, off sc1
	v_add_u32_e32 v2, v58, v174
	v_ashrrev_i32_e32 v3, 31, v2
	v_lshl_add_u64 v[2:3], v[2:3], 1, s[22:23]
	global_store_short v[2:3], v15, off sc1
	v_add_u32_e32 v2, v58, v175
	v_ashrrev_i32_e32 v3, 31, v2
	v_lshl_add_u64 v[2:3], v[2:3], 1, s[22:23]
	v_or_b32_e32 v58, 0x180, v61
	global_store_short v[2:3], v60, off sc1
	v_add_u32_e32 v2, v58, v174
	v_ashrrev_i32_e32 v3, 31, v2
	v_lshl_add_u64 v[2:3], v[2:3], 1, s[22:23]
	global_store_short v[2:3], v15, off sc1
	v_add_u32_e32 v2, v58, v175
	v_ashrrev_i32_e32 v3, 31, v2
	v_lshl_add_u64 v[2:3], v[2:3], 1, s[22:23]
	v_add_u32_e32 v58, 0x240, v61
	global_store_short v[2:3], v60, off sc1
	v_or_b32_e32 v2, v58, v174
	v_ashrrev_i32_e32 v3, 31, v2
	v_lshl_add_u64 v[2:3], v[2:3], 1, s[22:23]
	global_store_short v[2:3], v15, off sc1
	v_or_b32_e32 v2, v58, v175
	v_ashrrev_i32_e32 v3, 31, v2
	v_lshl_add_u64 v[2:3], v[2:3], 1, s[22:23]
	v_add_u32_e32 v58, 0x300, v61
	global_store_short v[2:3], v60, off sc1
	v_or_b32_e32 v2, v58, v174
	v_ashrrev_i32_e32 v3, 31, v2
	v_lshl_add_u64 v[2:3], v[2:3], 1, s[22:23]
	global_store_short v[2:3], v15, off sc1
	v_or_b32_e32 v2, v58, v175
	v_pk_mul_f32 v[58:59], v[68:69], v[68:69]
	v_ashrrev_i32_e32 v3, 31, v2
	v_add_f32_e32 v58, v59, v58
	ds_bpermute_b32 v59, v14, v58
	v_lshl_add_u64 v[2:3], v[2:3], 1, s[22:23]
	v_add_u32_e32 v62, 0x3c0, v61
	global_store_short v[2:3], v60, off sc1
	v_add_u32_e32 v2, v62, v174
	s_waitcnt lgkmcnt(0)
	v_add_f32_e32 v58, v58, v59
	ds_bpermute_b32 v59, v10, v58
	v_ashrrev_i32_e32 v3, 31, v2
	v_lshl_add_u64 v[2:3], v[2:3], 1, s[22:23]
	global_store_short v[2:3], v15, off sc1
	v_add_u32_e32 v2, v62, v175
	s_waitcnt lgkmcnt(0)
	v_add_f32_e32 v58, v58, v59
	ds_bpermute_b32 v59, v11, v58
	v_ashrrev_i32_e32 v3, 31, v2
	v_lshl_add_u64 v[2:3], v[2:3], 1, s[22:23]
	v_add_u32_e32 v62, 0x480, v61
	global_store_short v[2:3], v60, off sc1
	s_waitcnt lgkmcnt(0)
	v_add_f32_e32 v58, v58, v59
	ds_bpermute_b32 v59, v12, v58
	v_add_u32_e32 v2, v62, v174
	v_ashrrev_i32_e32 v3, 31, v2
	v_lshl_add_u64 v[2:3], v[2:3], 1, s[22:23]
	global_store_short v[2:3], v15, off sc1
	v_add_u32_e32 v2, v62, v175
	s_waitcnt lgkmcnt(0)
	v_add_f32_e32 v58, v58, v59
	v_ashrrev_i32_e32 v3, 31, v2
	ds_bpermute_b32 v59, v13, v58
	v_lshl_add_u64 v[2:3], v[2:3], 1, s[22:23]
	v_add_u32_e32 v61, 0x540, v61
	global_store_short v[2:3], v60, off sc1
	v_or_b32_e32 v2, v61, v174
	v_ashrrev_i32_e32 v3, 31, v2
	v_lshl_add_u64 v[2:3], v[2:3], 1, s[22:23]
	global_store_short v[2:3], v15, off sc1
	s_waitcnt lgkmcnt(0)
	v_add_f32_e32 v3, v58, v59
	v_fmamk_f32 v3, v3, 0x3c800000, v209
	v_rsq_f32_e32 v58, v3
	v_or_b32_e32 v2, v61, v175
	v_ashrrev_i32_e32 v3, 31, v2
	v_lshl_add_u64 v[2:3], v[2:3], 1, s[22:23]
	global_store_short v[2:3], v60, off sc1
	v_pk_mul_f32 v[2:3], v[0:1], v[58:59] op_sel_hi:[1,0]
	s_and_b64 vcc, exec, s[4:5]
	v_pk_mul_f32 v[2:3], v[68:69], v[2:3]
	s_mov_b64 s[80:81], -1
	s_cbranch_vccnz .LBB0_286
	v_add_u32_e32 v15, s76, v179
	v_lshl_or_b32 v58, v15, 6, v156
	v_ashrrev_i32_e32 v59, 31, v58
	v_lshl_add_u64 v[58:59], v[58:59], 2, s[24:25]
	s_mov_b64 s[80:81], 0
	global_store_dword v[58:59], v3, off sc1
	global_store_dword v[58:59], v2, off offset:128 sc1

.LBB0_288:
	v_cvt_pk_bf16_f32 v60, v2, s0
	v_add_u32_e32 v2, s11, v179
	v_mul_lo_u32 v61, v2, s94
	v_or_b32_e32 v2, v61, v174
	v_cvt_pk_bf16_f32 v15, v3, s0
	v_ashrrev_i32_e32 v3, 31, v2
	v_lshl_add_u64 v[2:3], v[2:3], 1, s[22:23]
	global_store_short v[2:3], v15, off sc1
	v_or_b32_e32 v2, v61, v175
	v_ashrrev_i32_e32 v3, 31, v2
	v_lshl_add_u64 v[2:3], v[2:3], 1, s[22:23]
	v_or_b32_e32 v58, 0xc0, v61
	global_store_short v[2:3], v60, off sc1
	v_add_u32_e32 v2, v58, v174
	v_ashrrev_i32_e32 v3, 31, v2
	v_lshl_add_u64 v[2:3], v[2:3], 1, s[22:23]
	global_store_short v[2:3], v15, off sc1
	v_add_u32_e32 v2, v58, v175
	v_ashrrev_i32_e32 v3, 31, v2
	v_lshl_add_u64 v[2:3], v[2:3], 1, s[22:23]
	v_or_b32_e32 v58, 0x180, v61
	global_store_short v[2:3], v60, off sc1
	v_add_u32_e32 v2, v58, v174
	v_ashrrev_i32_e32 v3, 31, v2
	v_lshl_add_u64 v[2:3], v[2:3], 1, s[22:23]
	global_store_short v[2:3], v15, off sc1
	v_add_u32_e32 v2, v58, v175
	v_ashrrev_i32_e32 v3, 31, v2
	v_lshl_add_u64 v[2:3], v[2:3], 1, s[22:23]
	v_add_u32_e32 v58, 0x240, v61
	global_store_short v[2:3], v60, off sc1
	v_or_b32_e32 v2, v58, v174
	v_ashrrev_i32_e32 v3, 31, v2
	v_lshl_add_u64 v[2:3], v[2:3], 1, s[22:23]
	global_store_short v[2:3], v15, off sc1
	v_or_b32_e32 v2, v58, v175
	v_ashrrev_i32_e32 v3, 31, v2
	v_lshl_add_u64 v[2:3], v[2:3], 1, s[22:23]
	v_add_u32_e32 v58, 0x300, v61
	global_store_short v[2:3], v60, off sc1
	v_or_b32_e32 v2, v58, v174
	v_ashrrev_i32_e32 v3, 31, v2
	v_lshl_add_u64 v[2:3], v[2:3], 1, s[22:23]
	global_store_short v[2:3], v15, off sc1
	v_or_b32_e32 v2, v58, v175
	v_pk_mul_f32 v[58:59], v[66:67], v[66:67]
	v_ashrrev_i32_e32 v3, 31, v2
	v_add_f32_e32 v58, v59, v58
	ds_bpermute_b32 v59, v14, v58
	v_lshl_add_u64 v[2:3], v[2:3], 1, s[22:23]
	v_add_u32_e32 v62, 0x3c0, v61
	global_store_short v[2:3], v60, off sc1
	v_add_u32_e32 v2, v62, v174
	s_waitcnt lgkmcnt(0)
	v_add_f32_e32 v58, v58, v59
	ds_bpermute_b32 v59, v10, v58
	v_ashrrev_i32_e32 v3, 31, v2
	v_lshl_add_u64 v[2:3], v[2:3], 1, s[22:23]
	global_store_short v[2:3], v15, off sc1
	v_add_u32_e32 v2, v62, v175
	s_waitcnt lgkmcnt(0)
	v_add_f32_e32 v58, v58, v59
	ds_bpermute_b32 v59, v11, v58
	v_ashrrev_i32_e32 v3, 31, v2
	v_lshl_add_u64 v[2:3], v[2:3], 1, s[22:23]
	v_add_u32_e32 v62, 0x480, v61
	global_store_short v[2:3], v60, off sc1
	s_waitcnt lgkmcnt(0)
	v_add_f32_e32 v58, v58, v59
	ds_bpermute_b32 v59, v12, v58
	v_add_u32_e32 v2, v62, v174
	v_ashrrev_i32_e32 v3, 31, v2
	v_lshl_add_u64 v[2:3], v[2:3], 1, s[22:23]
	global_store_short v[2:3], v15, off sc1
	v_add_u32_e32 v2, v62, v175
	s_waitcnt lgkmcnt(0)
	v_add_f32_e32 v58, v58, v59
	v_ashrrev_i32_e32 v3, 31, v2
	ds_bpermute_b32 v59, v13, v58
	v_lshl_add_u64 v[2:3], v[2:3], 1, s[22:23]
	v_add_u32_e32 v61, 0x540, v61
	global_store_short v[2:3], v60, off sc1
	v_or_b32_e32 v2, v61, v174
	v_ashrrev_i32_e32 v3, 31, v2
	v_lshl_add_u64 v[2:3], v[2:3], 1, s[22:23]
	global_store_short v[2:3], v15, off sc1
	s_waitcnt lgkmcnt(0)
	v_add_f32_e32 v3, v58, v59
	v_fmamk_f32 v3, v3, 0x3c800000, v209
	v_rsq_f32_e32 v58, v3
	v_or_b32_e32 v2, v61, v175
	v_ashrrev_i32_e32 v3, 31, v2
	v_lshl_add_u64 v[2:3], v[2:3], 1, s[22:23]
	global_store_short v[2:3], v60, off sc1
	v_pk_mul_f32 v[2:3], v[0:1], v[58:59] op_sel_hi:[1,0]
	s_and_b64 vcc, exec, s[4:5]
	v_pk_mul_f32 v[2:3], v[66:67], v[2:3]
	s_mov_b64 s[80:81], -1
	s_cbranch_vccnz .LBB0_290
	v_add_u32_e32 v15, s76, v180
	v_lshl_or_b32 v58, v15, 6, v156
	v_ashrrev_i32_e32 v59, 31, v58
	v_lshl_add_u64 v[58:59], v[58:59], 2, s[24:25]
	s_mov_b64 s[80:81], 0
	global_store_dword v[58:59], v3, off sc1
	global_store_dword v[58:59], v2, off offset:128 sc1

.LBB0_292:
	v_cvt_pk_bf16_f32 v60, v2, s0
	v_add_u32_e32 v2, s11, v180
	v_mul_lo_u32 v61, v2, s94
	v_or_b32_e32 v2, v61, v174
	v_cvt_pk_bf16_f32 v15, v3, s0
	v_ashrrev_i32_e32 v3, 31, v2
	v_lshl_add_u64 v[2:3], v[2:3], 1, s[22:23]
	global_store_short v[2:3], v15, off sc1
	v_or_b32_e32 v2, v61, v175
	v_ashrrev_i32_e32 v3, 31, v2
	v_lshl_add_u64 v[2:3], v[2:3], 1, s[22:23]
	v_or_b32_e32 v58, 0xc0, v61
	global_store_short v[2:3], v60, off sc1
	v_add_u32_e32 v2, v58, v174
	v_ashrrev_i32_e32 v3, 31, v2
	v_lshl_add_u64 v[2:3], v[2:3], 1, s[22:23]
	global_store_short v[2:3], v15, off sc1
	v_add_u32_e32 v2, v58, v175
	v_ashrrev_i32_e32 v3, 31, v2
	v_lshl_add_u64 v[2:3], v[2:3], 1, s[22:23]
	v_or_b32_e32 v58, 0x180, v61
	global_store_short v[2:3], v60, off sc1
	v_add_u32_e32 v2, v58, v174
	v_ashrrev_i32_e32 v3, 31, v2
	v_lshl_add_u64 v[2:3], v[2:3], 1, s[22:23]
	global_store_short v[2:3], v15, off sc1
	v_add_u32_e32 v2, v58, v175
	v_ashrrev_i32_e32 v3, 31, v2
	v_lshl_add_u64 v[2:3], v[2:3], 1, s[22:23]
	v_add_u32_e32 v58, 0x240, v61
	global_store_short v[2:3], v60, off sc1
	v_or_b32_e32 v2, v58, v174
	v_ashrrev_i32_e32 v3, 31, v2
	v_lshl_add_u64 v[2:3], v[2:3], 1, s[22:23]
	global_store_short v[2:3], v15, off sc1
	v_or_b32_e32 v2, v58, v175
	v_ashrrev_i32_e32 v3, 31, v2
	v_lshl_add_u64 v[2:3], v[2:3], 1, s[22:23]
	v_add_u32_e32 v58, 0x300, v61
	global_store_short v[2:3], v60, off sc1
	v_or_b32_e32 v2, v58, v174
	v_ashrrev_i32_e32 v3, 31, v2
	v_lshl_add_u64 v[2:3], v[2:3], 1, s[22:23]
	global_store_short v[2:3], v15, off sc1
	v_or_b32_e32 v2, v58, v175
	v_pk_mul_f32 v[58:59], v[64:65], v[64:65]
	v_ashrrev_i32_e32 v3, 31, v2
	v_add_f32_e32 v58, v59, v58
	ds_bpermute_b32 v59, v14, v58
	v_lshl_add_u64 v[2:3], v[2:3], 1, s[22:23]
	v_add_u32_e32 v62, 0x3c0, v61
	global_store_short v[2:3], v60, off sc1
	v_add_u32_e32 v2, v62, v174
	s_waitcnt lgkmcnt(0)
	v_add_f32_e32 v58, v58, v59
	ds_bpermute_b32 v59, v10, v58
	v_ashrrev_i32_e32 v3, 31, v2
	v_lshl_add_u64 v[2:3], v[2:3], 1, s[22:23]
	global_store_short v[2:3], v15, off sc1
	v_add_u32_e32 v2, v62, v175
	s_waitcnt lgkmcnt(0)
	v_add_f32_e32 v58, v58, v59
	ds_bpermute_b32 v59, v11, v58
	v_ashrrev_i32_e32 v3, 31, v2
	v_lshl_add_u64 v[2:3], v[2:3], 1, s[22:23]
	v_add_u32_e32 v62, 0x480, v61
	global_store_short v[2:3], v60, off sc1
	s_waitcnt lgkmcnt(0)
	v_add_f32_e32 v58, v58, v59
	ds_bpermute_b32 v59, v12, v58
	v_add_u32_e32 v2, v62, v174
	v_ashrrev_i32_e32 v3, 31, v2
	v_lshl_add_u64 v[2:3], v[2:3], 1, s[22:23]
	global_store_short v[2:3], v15, off sc1
	v_add_u32_e32 v2, v62, v175
	s_waitcnt lgkmcnt(0)
	v_add_f32_e32 v58, v58, v59
	v_ashrrev_i32_e32 v3, 31, v2
	ds_bpermute_b32 v59, v13, v58
	v_lshl_add_u64 v[2:3], v[2:3], 1, s[22:23]
	v_add_u32_e32 v61, 0x540, v61
	global_store_short v[2:3], v60, off sc1
	v_or_b32_e32 v2, v61, v174
	v_ashrrev_i32_e32 v3, 31, v2
	v_lshl_add_u64 v[2:3], v[2:3], 1, s[22:23]
	global_store_short v[2:3], v15, off sc1
	s_waitcnt lgkmcnt(0)
	v_add_f32_e32 v3, v58, v59
	v_fmamk_f32 v3, v3, 0x3c800000, v209
	v_rsq_f32_e32 v58, v3
	v_or_b32_e32 v2, v61, v175
	v_ashrrev_i32_e32 v3, 31, v2
	v_lshl_add_u64 v[2:3], v[2:3], 1, s[22:23]
	global_store_short v[2:3], v60, off sc1
	v_pk_mul_f32 v[2:3], v[0:1], v[58:59] op_sel_hi:[1,0]
	s_and_b64 vcc, exec, s[4:5]
	v_pk_mul_f32 v[2:3], v[64:65], v[2:3]
	s_mov_b64 s[80:81], -1
	s_cbranch_vccnz .LBB0_294
	v_add_u32_e32 v15, s76, v181
	v_lshl_or_b32 v58, v15, 6, v156
	v_ashrrev_i32_e32 v59, 31, v58
	v_lshl_add_u64 v[58:59], v[58:59], 2, s[24:25]
	s_mov_b64 s[80:81], 0
	global_store_dword v[58:59], v3, off sc1
	global_store_dword v[58:59], v2, off offset:128 sc1

.LBB0_296:
	v_cvt_pk_bf16_f32 v60, v2, s0
	v_add_u32_e32 v2, s11, v181
	v_mul_lo_u32 v61, v2, s94
	v_or_b32_e32 v2, v61, v174
	v_cvt_pk_bf16_f32 v15, v3, s0
	v_ashrrev_i32_e32 v3, 31, v2
	v_lshl_add_u64 v[2:3], v[2:3], 1, s[22:23]
	global_store_short v[2:3], v15, off sc1
	v_or_b32_e32 v2, v61, v175
	v_ashrrev_i32_e32 v3, 31, v2
	v_lshl_add_u64 v[2:3], v[2:3], 1, s[22:23]
	v_or_b32_e32 v58, 0xc0, v61
	global_store_short v[2:3], v60, off sc1
	v_add_u32_e32 v2, v58, v174
	v_ashrrev_i32_e32 v3, 31, v2
	v_lshl_add_u64 v[2:3], v[2:3], 1, s[22:23]
	global_store_short v[2:3], v15, off sc1
	v_add_u32_e32 v2, v58, v175
	v_ashrrev_i32_e32 v3, 31, v2
	v_lshl_add_u64 v[2:3], v[2:3], 1, s[22:23]
	v_or_b32_e32 v58, 0x180, v61
	global_store_short v[2:3], v60, off sc1
	v_add_u32_e32 v2, v58, v174
	v_ashrrev_i32_e32 v3, 31, v2
	v_lshl_add_u64 v[2:3], v[2:3], 1, s[22:23]
	global_store_short v[2:3], v15, off sc1
	v_add_u32_e32 v2, v58, v175
	v_ashrrev_i32_e32 v3, 31, v2
	v_lshl_add_u64 v[2:3], v[2:3], 1, s[22:23]
	v_add_u32_e32 v58, 0x240, v61
	global_store_short v[2:3], v60, off sc1
	v_or_b32_e32 v2, v58, v174
	v_ashrrev_i32_e32 v3, 31, v2
	v_lshl_add_u64 v[2:3], v[2:3], 1, s[22:23]
	global_store_short v[2:3], v15, off sc1
	v_or_b32_e32 v2, v58, v175
	v_ashrrev_i32_e32 v3, 31, v2
	v_lshl_add_u64 v[2:3], v[2:3], 1, s[22:23]
	v_add_u32_e32 v58, 0x300, v61
	global_store_short v[2:3], v60, off sc1
	v_or_b32_e32 v2, v58, v174
	v_ashrrev_i32_e32 v3, 31, v2
	v_lshl_add_u64 v[2:3], v[2:3], 1, s[22:23]
	global_store_short v[2:3], v15, off sc1
	v_or_b32_e32 v2, v58, v175
	v_pk_mul_f32 v[58:59], v[54:55], v[54:55]
	v_ashrrev_i32_e32 v3, 31, v2
	v_add_f32_e32 v58, v59, v58
	ds_bpermute_b32 v59, v14, v58
	v_lshl_add_u64 v[2:3], v[2:3], 1, s[22:23]
	v_add_u32_e32 v62, 0x3c0, v61
	global_store_short v[2:3], v60, off sc1
	v_add_u32_e32 v2, v62, v174
	s_waitcnt lgkmcnt(0)
	v_add_f32_e32 v58, v58, v59
	ds_bpermute_b32 v59, v10, v58
	v_ashrrev_i32_e32 v3, 31, v2
	v_lshl_add_u64 v[2:3], v[2:3], 1, s[22:23]
	global_store_short v[2:3], v15, off sc1
	v_add_u32_e32 v2, v62, v175
	s_waitcnt lgkmcnt(0)
	v_add_f32_e32 v58, v58, v59
	ds_bpermute_b32 v59, v11, v58
	v_ashrrev_i32_e32 v3, 31, v2
	v_lshl_add_u64 v[2:3], v[2:3], 1, s[22:23]
	v_add_u32_e32 v62, 0x480, v61
	global_store_short v[2:3], v60, off sc1
	s_waitcnt lgkmcnt(0)
	v_add_f32_e32 v58, v58, v59
	ds_bpermute_b32 v59, v12, v58
	v_add_u32_e32 v2, v62, v174
	v_ashrrev_i32_e32 v3, 31, v2
	v_lshl_add_u64 v[2:3], v[2:3], 1, s[22:23]
	global_store_short v[2:3], v15, off sc1
	v_add_u32_e32 v2, v62, v175
	s_waitcnt lgkmcnt(0)
	v_add_f32_e32 v58, v58, v59
	v_ashrrev_i32_e32 v3, 31, v2
	ds_bpermute_b32 v59, v13, v58
	v_lshl_add_u64 v[2:3], v[2:3], 1, s[22:23]
	v_add_u32_e32 v61, 0x540, v61
	global_store_short v[2:3], v60, off sc1
	v_or_b32_e32 v2, v61, v174
	v_ashrrev_i32_e32 v3, 31, v2
	v_lshl_add_u64 v[2:3], v[2:3], 1, s[22:23]
	global_store_short v[2:3], v15, off sc1
	s_waitcnt lgkmcnt(0)
	v_add_f32_e32 v3, v58, v59
	v_fmamk_f32 v3, v3, 0x3c800000, v209
	v_rsq_f32_e32 v58, v3
	v_or_b32_e32 v2, v61, v175
	v_ashrrev_i32_e32 v3, 31, v2
	v_lshl_add_u64 v[2:3], v[2:3], 1, s[22:23]
	global_store_short v[2:3], v60, off sc1
	v_pk_mul_f32 v[2:3], v[0:1], v[58:59] op_sel_hi:[1,0]
	s_and_b64 vcc, exec, s[4:5]
	v_pk_mul_f32 v[2:3], v[54:55], v[2:3]
	s_mov_b64 s[80:81], -1
	s_cbranch_vccnz .LBB0_298
	v_add_u32_e32 v15, s76, v182
	v_lshl_or_b32 v58, v15, 6, v156
	v_ashrrev_i32_e32 v59, 31, v58
	v_lshl_add_u64 v[58:59], v[58:59], 2, s[24:25]
	s_mov_b64 s[80:81], 0
	global_store_dword v[58:59], v3, off sc1
	global_store_dword v[58:59], v2, off offset:128 sc1

.LBB0_300:
	v_cvt_pk_bf16_f32 v60, v2, s0
	v_add_u32_e32 v2, s11, v182
	v_mul_lo_u32 v61, v2, s94
	v_or_b32_e32 v2, v61, v174
	v_cvt_pk_bf16_f32 v15, v3, s0
	v_ashrrev_i32_e32 v3, 31, v2
	v_lshl_add_u64 v[2:3], v[2:3], 1, s[22:23]
	global_store_short v[2:3], v15, off sc1
	v_or_b32_e32 v2, v61, v175
	v_ashrrev_i32_e32 v3, 31, v2
	v_lshl_add_u64 v[2:3], v[2:3], 1, s[22:23]
	v_or_b32_e32 v58, 0xc0, v61
	global_store_short v[2:3], v60, off sc1
	v_add_u32_e32 v2, v58, v174
	v_ashrrev_i32_e32 v3, 31, v2
	v_lshl_add_u64 v[2:3], v[2:3], 1, s[22:23]
	global_store_short v[2:3], v15, off sc1
	v_add_u32_e32 v2, v58, v175
	v_ashrrev_i32_e32 v3, 31, v2
	v_lshl_add_u64 v[2:3], v[2:3], 1, s[22:23]
	v_or_b32_e32 v58, 0x180, v61
	global_store_short v[2:3], v60, off sc1
	v_add_u32_e32 v2, v58, v174
	v_ashrrev_i32_e32 v3, 31, v2
	v_lshl_add_u64 v[2:3], v[2:3], 1, s[22:23]
	global_store_short v[2:3], v15, off sc1
	v_add_u32_e32 v2, v58, v175
	v_ashrrev_i32_e32 v3, 31, v2
	v_lshl_add_u64 v[2:3], v[2:3], 1, s[22:23]
	v_add_u32_e32 v58, 0x240, v61
	global_store_short v[2:3], v60, off sc1
	v_or_b32_e32 v2, v58, v174
	v_ashrrev_i32_e32 v3, 31, v2
	v_lshl_add_u64 v[2:3], v[2:3], 1, s[22:23]
	global_store_short v[2:3], v15, off sc1
	v_or_b32_e32 v2, v58, v175
	v_ashrrev_i32_e32 v3, 31, v2
	v_lshl_add_u64 v[2:3], v[2:3], 1, s[22:23]
	v_add_u32_e32 v58, 0x300, v61
	global_store_short v[2:3], v60, off sc1
	v_or_b32_e32 v2, v58, v174
	v_ashrrev_i32_e32 v3, 31, v2
	v_lshl_add_u64 v[2:3], v[2:3], 1, s[22:23]
	global_store_short v[2:3], v15, off sc1
	v_or_b32_e32 v2, v58, v175
	v_pk_mul_f32 v[58:59], v[52:53], v[52:53]
	v_ashrrev_i32_e32 v3, 31, v2
	v_add_f32_e32 v58, v59, v58
	ds_bpermute_b32 v59, v14, v58
	v_lshl_add_u64 v[2:3], v[2:3], 1, s[22:23]
	v_add_u32_e32 v62, 0x3c0, v61
	global_store_short v[2:3], v60, off sc1
	v_add_u32_e32 v2, v62, v174
	s_waitcnt lgkmcnt(0)
	v_add_f32_e32 v58, v58, v59
	ds_bpermute_b32 v59, v10, v58
	v_ashrrev_i32_e32 v3, 31, v2
	v_lshl_add_u64 v[2:3], v[2:3], 1, s[22:23]
	global_store_short v[2:3], v15, off sc1
	v_add_u32_e32 v2, v62, v175
	s_waitcnt lgkmcnt(0)
	v_add_f32_e32 v58, v58, v59
	ds_bpermute_b32 v59, v11, v58
	v_ashrrev_i32_e32 v3, 31, v2
	v_lshl_add_u64 v[2:3], v[2:3], 1, s[22:23]
	v_add_u32_e32 v62, 0x480, v61
	global_store_short v[2:3], v60, off sc1
	s_waitcnt lgkmcnt(0)
	v_add_f32_e32 v58, v58, v59
	ds_bpermute_b32 v59, v12, v58
	v_add_u32_e32 v2, v62, v174
	v_ashrrev_i32_e32 v3, 31, v2
	v_lshl_add_u64 v[2:3], v[2:3], 1, s[22:23]
	global_store_short v[2:3], v15, off sc1
	v_add_u32_e32 v2, v62, v175
	s_waitcnt lgkmcnt(0)
	v_add_f32_e32 v58, v58, v59
	v_ashrrev_i32_e32 v3, 31, v2
	ds_bpermute_b32 v59, v13, v58
	v_lshl_add_u64 v[2:3], v[2:3], 1, s[22:23]
	v_add_u32_e32 v61, 0x540, v61
	global_store_short v[2:3], v60, off sc1
	v_or_b32_e32 v2, v61, v174
	v_ashrrev_i32_e32 v3, 31, v2
	v_lshl_add_u64 v[2:3], v[2:3], 1, s[22:23]
	global_store_short v[2:3], v15, off sc1
	s_waitcnt lgkmcnt(0)
	v_add_f32_e32 v3, v58, v59
	v_fmamk_f32 v3, v3, 0x3c800000, v209
	v_rsq_f32_e32 v58, v3
	v_or_b32_e32 v2, v61, v175
	v_ashrrev_i32_e32 v3, 31, v2
	v_lshl_add_u64 v[2:3], v[2:3], 1, s[22:23]
	global_store_short v[2:3], v60, off sc1
	v_pk_mul_f32 v[2:3], v[0:1], v[58:59] op_sel_hi:[1,0]
	s_and_b64 vcc, exec, s[4:5]
	v_pk_mul_f32 v[2:3], v[52:53], v[2:3]
	s_mov_b64 s[80:81], -1
	s_cbranch_vccnz .LBB0_302
	v_add_u32_e32 v15, s76, v183
	v_lshl_or_b32 v58, v15, 6, v156
	v_ashrrev_i32_e32 v59, 31, v58
	v_lshl_add_u64 v[58:59], v[58:59], 2, s[24:25]
	s_mov_b64 s[80:81], 0
	global_store_dword v[58:59], v3, off sc1
	global_store_dword v[58:59], v2, off offset:128 sc1

.LBB0_304:
	v_cvt_pk_bf16_f32 v60, v2, s0
	v_add_u32_e32 v2, s11, v183
	v_mul_lo_u32 v61, v2, s94
	v_or_b32_e32 v2, v61, v174
	v_cvt_pk_bf16_f32 v15, v3, s0
	v_ashrrev_i32_e32 v3, 31, v2
	v_lshl_add_u64 v[2:3], v[2:3], 1, s[22:23]
	global_store_short v[2:3], v15, off sc1
	v_or_b32_e32 v2, v61, v175
	v_ashrrev_i32_e32 v3, 31, v2
	v_lshl_add_u64 v[2:3], v[2:3], 1, s[22:23]
	v_or_b32_e32 v58, 0xc0, v61
	global_store_short v[2:3], v60, off sc1
	v_add_u32_e32 v2, v58, v174
	v_ashrrev_i32_e32 v3, 31, v2
	v_lshl_add_u64 v[2:3], v[2:3], 1, s[22:23]
	global_store_short v[2:3], v15, off sc1
	v_add_u32_e32 v2, v58, v175
	v_ashrrev_i32_e32 v3, 31, v2
	v_lshl_add_u64 v[2:3], v[2:3], 1, s[22:23]
	v_or_b32_e32 v58, 0x180, v61
	global_store_short v[2:3], v60, off sc1
	v_add_u32_e32 v2, v58, v174
	v_ashrrev_i32_e32 v3, 31, v2
	v_lshl_add_u64 v[2:3], v[2:3], 1, s[22:23]
	global_store_short v[2:3], v15, off sc1
	v_add_u32_e32 v2, v58, v175
	v_ashrrev_i32_e32 v3, 31, v2
	v_lshl_add_u64 v[2:3], v[2:3], 1, s[22:23]
	v_add_u32_e32 v58, 0x240, v61
	global_store_short v[2:3], v60, off sc1
	v_or_b32_e32 v2, v58, v174
	v_ashrrev_i32_e32 v3, 31, v2
	v_lshl_add_u64 v[2:3], v[2:3], 1, s[22:23]
	global_store_short v[2:3], v15, off sc1
	v_or_b32_e32 v2, v58, v175
	v_ashrrev_i32_e32 v3, 31, v2
	v_lshl_add_u64 v[2:3], v[2:3], 1, s[22:23]
	v_add_u32_e32 v58, 0x300, v61
	global_store_short v[2:3], v60, off sc1
	v_or_b32_e32 v2, v58, v174
	v_ashrrev_i32_e32 v3, 31, v2
	v_lshl_add_u64 v[2:3], v[2:3], 1, s[22:23]
	global_store_short v[2:3], v15, off sc1
	v_or_b32_e32 v2, v58, v175
	v_pk_mul_f32 v[58:59], v[50:51], v[50:51]
	v_ashrrev_i32_e32 v3, 31, v2
	v_add_f32_e32 v58, v59, v58
	ds_bpermute_b32 v59, v14, v58
	v_lshl_add_u64 v[2:3], v[2:3], 1, s[22:23]
	v_add_u32_e32 v62, 0x3c0, v61
	global_store_short v[2:3], v60, off sc1
	v_add_u32_e32 v2, v62, v174
	s_waitcnt lgkmcnt(0)
	v_add_f32_e32 v58, v58, v59
	ds_bpermute_b32 v59, v10, v58
	v_ashrrev_i32_e32 v3, 31, v2
	v_lshl_add_u64 v[2:3], v[2:3], 1, s[22:23]
	global_store_short v[2:3], v15, off sc1
	v_add_u32_e32 v2, v62, v175
	s_waitcnt lgkmcnt(0)
	v_add_f32_e32 v58, v58, v59
	ds_bpermute_b32 v59, v11, v58
	v_ashrrev_i32_e32 v3, 31, v2
	v_lshl_add_u64 v[2:3], v[2:3], 1, s[22:23]
	v_add_u32_e32 v62, 0x480, v61
	global_store_short v[2:3], v60, off sc1
	s_waitcnt lgkmcnt(0)
	v_add_f32_e32 v58, v58, v59
	ds_bpermute_b32 v59, v12, v58
	v_add_u32_e32 v2, v62, v174
	v_ashrrev_i32_e32 v3, 31, v2
	v_lshl_add_u64 v[2:3], v[2:3], 1, s[22:23]
	global_store_short v[2:3], v15, off sc1
	v_add_u32_e32 v2, v62, v175
	s_waitcnt lgkmcnt(0)
	v_add_f32_e32 v58, v58, v59
	v_ashrrev_i32_e32 v3, 31, v2
	ds_bpermute_b32 v59, v13, v58
	v_lshl_add_u64 v[2:3], v[2:3], 1, s[22:23]
	v_add_u32_e32 v61, 0x540, v61
	global_store_short v[2:3], v60, off sc1
	v_or_b32_e32 v2, v61, v174
	v_ashrrev_i32_e32 v3, 31, v2
	v_lshl_add_u64 v[2:3], v[2:3], 1, s[22:23]
	global_store_short v[2:3], v15, off sc1
	s_waitcnt lgkmcnt(0)
	v_add_f32_e32 v3, v58, v59
	v_fmamk_f32 v3, v3, 0x3c800000, v209
	v_rsq_f32_e32 v58, v3
	v_or_b32_e32 v2, v61, v175
	v_ashrrev_i32_e32 v3, 31, v2
	v_lshl_add_u64 v[2:3], v[2:3], 1, s[22:23]
	global_store_short v[2:3], v60, off sc1
	v_pk_mul_f32 v[2:3], v[0:1], v[58:59] op_sel_hi:[1,0]
	s_and_b64 vcc, exec, s[4:5]
	v_pk_mul_f32 v[2:3], v[50:51], v[2:3]
	s_mov_b64 s[80:81], -1
	s_cbranch_vccnz .LBB0_306
	v_add_u32_e32 v15, s76, v184
	v_lshl_or_b32 v58, v15, 6, v156
	v_ashrrev_i32_e32 v59, 31, v58
	v_lshl_add_u64 v[58:59], v[58:59], 2, s[24:25]
	s_mov_b64 s[80:81], 0
	global_store_dword v[58:59], v3, off sc1
	global_store_dword v[58:59], v2, off offset:128 sc1

.LBB0_308:
	v_cvt_pk_bf16_f32 v60, v2, s0
	v_add_u32_e32 v2, s11, v184
	v_mul_lo_u32 v61, v2, s94
	v_or_b32_e32 v2, v61, v174
	v_cvt_pk_bf16_f32 v15, v3, s0
	v_ashrrev_i32_e32 v3, 31, v2
	v_lshl_add_u64 v[2:3], v[2:3], 1, s[22:23]
	global_store_short v[2:3], v15, off sc1
	v_or_b32_e32 v2, v61, v175
	v_ashrrev_i32_e32 v3, 31, v2
	v_lshl_add_u64 v[2:3], v[2:3], 1, s[22:23]
	v_or_b32_e32 v58, 0xc0, v61
	global_store_short v[2:3], v60, off sc1
	v_add_u32_e32 v2, v58, v174
	v_ashrrev_i32_e32 v3, 31, v2
	v_lshl_add_u64 v[2:3], v[2:3], 1, s[22:23]
	global_store_short v[2:3], v15, off sc1
	v_add_u32_e32 v2, v58, v175
	v_ashrrev_i32_e32 v3, 31, v2
	v_lshl_add_u64 v[2:3], v[2:3], 1, s[22:23]
	v_or_b32_e32 v58, 0x180, v61
	global_store_short v[2:3], v60, off sc1
	v_add_u32_e32 v2, v58, v174
	v_ashrrev_i32_e32 v3, 31, v2
	v_lshl_add_u64 v[2:3], v[2:3], 1, s[22:23]
	global_store_short v[2:3], v15, off sc1
	v_add_u32_e32 v2, v58, v175
	v_ashrrev_i32_e32 v3, 31, v2
	v_lshl_add_u64 v[2:3], v[2:3], 1, s[22:23]
	v_add_u32_e32 v58, 0x240, v61
	global_store_short v[2:3], v60, off sc1
	v_or_b32_e32 v2, v58, v174
	v_ashrrev_i32_e32 v3, 31, v2
	v_lshl_add_u64 v[2:3], v[2:3], 1, s[22:23]
	global_store_short v[2:3], v15, off sc1
	v_or_b32_e32 v2, v58, v175
	v_ashrrev_i32_e32 v3, 31, v2
	v_lshl_add_u64 v[2:3], v[2:3], 1, s[22:23]
	v_add_u32_e32 v58, 0x300, v61
	global_store_short v[2:3], v60, off sc1
	v_or_b32_e32 v2, v58, v174
	v_ashrrev_i32_e32 v3, 31, v2
	v_lshl_add_u64 v[2:3], v[2:3], 1, s[22:23]
	global_store_short v[2:3], v15, off sc1
	v_or_b32_e32 v2, v58, v175
	v_pk_mul_f32 v[58:59], v[48:49], v[48:49]
	v_ashrrev_i32_e32 v3, 31, v2
	v_add_f32_e32 v58, v59, v58
	ds_bpermute_b32 v59, v14, v58
	v_lshl_add_u64 v[2:3], v[2:3], 1, s[22:23]
	v_add_u32_e32 v62, 0x3c0, v61
	global_store_short v[2:3], v60, off sc1
	v_add_u32_e32 v2, v62, v174
	s_waitcnt lgkmcnt(0)
	v_add_f32_e32 v58, v58, v59
	ds_bpermute_b32 v59, v10, v58
	v_ashrrev_i32_e32 v3, 31, v2
	v_lshl_add_u64 v[2:3], v[2:3], 1, s[22:23]
	global_store_short v[2:3], v15, off sc1
	v_add_u32_e32 v2, v62, v175
	s_waitcnt lgkmcnt(0)
	v_add_f32_e32 v58, v58, v59
	ds_bpermute_b32 v59, v11, v58
	v_ashrrev_i32_e32 v3, 31, v2
	v_lshl_add_u64 v[2:3], v[2:3], 1, s[22:23]
	v_add_u32_e32 v62, 0x480, v61
	global_store_short v[2:3], v60, off sc1
	s_waitcnt lgkmcnt(0)
	v_add_f32_e32 v58, v58, v59
	ds_bpermute_b32 v59, v12, v58
	v_add_u32_e32 v2, v62, v174
	v_ashrrev_i32_e32 v3, 31, v2
	v_lshl_add_u64 v[2:3], v[2:3], 1, s[22:23]
	global_store_short v[2:3], v15, off sc1
	v_add_u32_e32 v2, v62, v175
	s_waitcnt lgkmcnt(0)
	v_add_f32_e32 v58, v58, v59
	v_ashrrev_i32_e32 v3, 31, v2
	ds_bpermute_b32 v59, v13, v58
	v_lshl_add_u64 v[2:3], v[2:3], 1, s[22:23]
	v_add_u32_e32 v61, 0x540, v61
	global_store_short v[2:3], v60, off sc1
	v_or_b32_e32 v2, v61, v174
	v_ashrrev_i32_e32 v3, 31, v2
	v_lshl_add_u64 v[2:3], v[2:3], 1, s[22:23]
	global_store_short v[2:3], v15, off sc1
	s_waitcnt lgkmcnt(0)
	v_add_f32_e32 v3, v58, v59
	v_fmamk_f32 v3, v3, 0x3c800000, v209
	v_rsq_f32_e32 v58, v3
	v_or_b32_e32 v2, v61, v175
	v_ashrrev_i32_e32 v3, 31, v2
	v_lshl_add_u64 v[2:3], v[2:3], 1, s[22:23]
	global_store_short v[2:3], v60, off sc1
	v_pk_mul_f32 v[2:3], v[0:1], v[58:59] op_sel_hi:[1,0]
	s_and_b64 vcc, exec, s[4:5]
	v_pk_mul_f32 v[2:3], v[48:49], v[2:3]
	s_mov_b64 s[80:81], -1
	s_cbranch_vccnz .LBB0_310
	v_add_u32_e32 v15, s76, v185
	v_lshl_or_b32 v58, v15, 6, v156
	v_ashrrev_i32_e32 v59, 31, v58
	v_lshl_add_u64 v[58:59], v[58:59], 2, s[24:25]
	s_mov_b64 s[80:81], 0
	global_store_dword v[58:59], v3, off sc1
	global_store_dword v[58:59], v2, off offset:128 sc1

.LBB0_312:
	v_cvt_pk_bf16_f32 v60, v2, s0
	v_add_u32_e32 v2, s11, v185
	v_mul_lo_u32 v61, v2, s94
	v_or_b32_e32 v2, v61, v174
	v_cvt_pk_bf16_f32 v15, v3, s0
	v_ashrrev_i32_e32 v3, 31, v2
	v_lshl_add_u64 v[2:3], v[2:3], 1, s[22:23]
	global_store_short v[2:3], v15, off sc1
	v_or_b32_e32 v2, v61, v175
	v_ashrrev_i32_e32 v3, 31, v2
	v_lshl_add_u64 v[2:3], v[2:3], 1, s[22:23]
	v_or_b32_e32 v58, 0xc0, v61
	global_store_short v[2:3], v60, off sc1
	v_add_u32_e32 v2, v58, v174
	v_ashrrev_i32_e32 v3, 31, v2
	v_lshl_add_u64 v[2:3], v[2:3], 1, s[22:23]
	global_store_short v[2:3], v15, off sc1
	v_add_u32_e32 v2, v58, v175
	v_ashrrev_i32_e32 v3, 31, v2
	v_lshl_add_u64 v[2:3], v[2:3], 1, s[22:23]
	v_or_b32_e32 v58, 0x180, v61
	global_store_short v[2:3], v60, off sc1
	v_add_u32_e32 v2, v58, v174
	v_ashrrev_i32_e32 v3, 31, v2
	v_lshl_add_u64 v[2:3], v[2:3], 1, s[22:23]
	global_store_short v[2:3], v15, off sc1
	v_add_u32_e32 v2, v58, v175
	v_ashrrev_i32_e32 v3, 31, v2
	v_lshl_add_u64 v[2:3], v[2:3], 1, s[22:23]
	v_add_u32_e32 v58, 0x240, v61
	global_store_short v[2:3], v60, off sc1
	v_or_b32_e32 v2, v58, v174
	v_ashrrev_i32_e32 v3, 31, v2
	v_lshl_add_u64 v[2:3], v[2:3], 1, s[22:23]
	global_store_short v[2:3], v15, off sc1
	v_or_b32_e32 v2, v58, v175
	v_ashrrev_i32_e32 v3, 31, v2
	v_lshl_add_u64 v[2:3], v[2:3], 1, s[22:23]
	v_add_u32_e32 v58, 0x300, v61
	global_store_short v[2:3], v60, off sc1
	v_or_b32_e32 v2, v58, v174
	v_ashrrev_i32_e32 v3, 31, v2
	v_lshl_add_u64 v[2:3], v[2:3], 1, s[22:23]
	global_store_short v[2:3], v15, off sc1
	v_or_b32_e32 v2, v58, v175
	v_pk_mul_f32 v[58:59], v[40:41], v[40:41]
	v_ashrrev_i32_e32 v3, 31, v2
	v_add_f32_e32 v58, v59, v58
	ds_bpermute_b32 v59, v14, v58
	v_lshl_add_u64 v[2:3], v[2:3], 1, s[22:23]
	v_add_u32_e32 v62, 0x3c0, v61
	global_store_short v[2:3], v60, off sc1
	v_add_u32_e32 v2, v62, v174
	s_waitcnt lgkmcnt(0)
	v_add_f32_e32 v58, v58, v59
	ds_bpermute_b32 v59, v10, v58
	v_ashrrev_i32_e32 v3, 31, v2
	v_lshl_add_u64 v[2:3], v[2:3], 1, s[22:23]
	global_store_short v[2:3], v15, off sc1
	v_add_u32_e32 v2, v62, v175
	s_waitcnt lgkmcnt(0)
	v_add_f32_e32 v58, v58, v59
	ds_bpermute_b32 v59, v11, v58
	v_ashrrev_i32_e32 v3, 31, v2
	v_lshl_add_u64 v[2:3], v[2:3], 1, s[22:23]
	v_add_u32_e32 v62, 0x480, v61
	global_store_short v[2:3], v60, off sc1
	s_waitcnt lgkmcnt(0)
	v_add_f32_e32 v58, v58, v59
	ds_bpermute_b32 v59, v12, v58
	v_add_u32_e32 v2, v62, v174
	v_ashrrev_i32_e32 v3, 31, v2
	v_lshl_add_u64 v[2:3], v[2:3], 1, s[22:23]
	global_store_short v[2:3], v15, off sc1
	v_add_u32_e32 v2, v62, v175
	s_waitcnt lgkmcnt(0)
	v_add_f32_e32 v58, v58, v59
	v_ashrrev_i32_e32 v3, 31, v2
	ds_bpermute_b32 v59, v13, v58
	v_lshl_add_u64 v[2:3], v[2:3], 1, s[22:23]
	v_add_u32_e32 v61, 0x540, v61
	global_store_short v[2:3], v60, off sc1
	v_or_b32_e32 v2, v61, v174
	v_ashrrev_i32_e32 v3, 31, v2
	v_lshl_add_u64 v[2:3], v[2:3], 1, s[22:23]
	global_store_short v[2:3], v15, off sc1
	s_waitcnt lgkmcnt(0)
	v_add_f32_e32 v3, v58, v59
	v_fmamk_f32 v3, v3, 0x3c800000, v209
	v_rsq_f32_e32 v58, v3
	v_or_b32_e32 v2, v61, v175
	v_ashrrev_i32_e32 v3, 31, v2
	v_lshl_add_u64 v[2:3], v[2:3], 1, s[22:23]
	global_store_short v[2:3], v60, off sc1
	v_pk_mul_f32 v[2:3], v[0:1], v[58:59] op_sel_hi:[1,0]
	s_and_b64 vcc, exec, s[4:5]
	v_pk_mul_f32 v[2:3], v[40:41], v[2:3]
	s_mov_b64 s[80:81], -1
	s_cbranch_vccnz .LBB0_314
	v_add_u32_e32 v15, s76, v186
	v_lshl_or_b32 v58, v15, 6, v156
	v_ashrrev_i32_e32 v59, 31, v58
	v_lshl_add_u64 v[58:59], v[58:59], 2, s[24:25]
	s_mov_b64 s[80:81], 0
	global_store_dword v[58:59], v3, off sc1
	global_store_dword v[58:59], v2, off offset:128 sc1

.LBB0_316:
	v_cvt_pk_bf16_f32 v60, v2, s0
	v_add_u32_e32 v2, s11, v186
	v_mul_lo_u32 v61, v2, s94
	v_or_b32_e32 v2, v61, v174
	v_cvt_pk_bf16_f32 v15, v3, s0
	v_ashrrev_i32_e32 v3, 31, v2
	v_lshl_add_u64 v[2:3], v[2:3], 1, s[22:23]
	global_store_short v[2:3], v15, off sc1
	v_or_b32_e32 v2, v61, v175
	v_ashrrev_i32_e32 v3, 31, v2
	v_lshl_add_u64 v[2:3], v[2:3], 1, s[22:23]
	v_or_b32_e32 v58, 0xc0, v61
	global_store_short v[2:3], v60, off sc1
	v_add_u32_e32 v2, v58, v174
	v_ashrrev_i32_e32 v3, 31, v2
	v_lshl_add_u64 v[2:3], v[2:3], 1, s[22:23]
	global_store_short v[2:3], v15, off sc1
	v_add_u32_e32 v2, v58, v175
	v_ashrrev_i32_e32 v3, 31, v2
	v_lshl_add_u64 v[2:3], v[2:3], 1, s[22:23]
	v_or_b32_e32 v58, 0x180, v61
	global_store_short v[2:3], v60, off sc1
	v_add_u32_e32 v2, v58, v174
	v_ashrrev_i32_e32 v3, 31, v2
	v_lshl_add_u64 v[2:3], v[2:3], 1, s[22:23]
	global_store_short v[2:3], v15, off sc1
	v_add_u32_e32 v2, v58, v175
	v_ashrrev_i32_e32 v3, 31, v2
	v_lshl_add_u64 v[2:3], v[2:3], 1, s[22:23]
	v_add_u32_e32 v58, 0x240, v61
	global_store_short v[2:3], v60, off sc1
	v_or_b32_e32 v2, v58, v174
	v_ashrrev_i32_e32 v3, 31, v2
	v_lshl_add_u64 v[2:3], v[2:3], 1, s[22:23]
	global_store_short v[2:3], v15, off sc1
	v_or_b32_e32 v2, v58, v175
	v_ashrrev_i32_e32 v3, 31, v2
	v_lshl_add_u64 v[2:3], v[2:3], 1, s[22:23]
	v_add_u32_e32 v58, 0x300, v61
	global_store_short v[2:3], v60, off sc1
	v_or_b32_e32 v2, v58, v174
	v_ashrrev_i32_e32 v3, 31, v2
	v_lshl_add_u64 v[2:3], v[2:3], 1, s[22:23]
	global_store_short v[2:3], v15, off sc1
	v_or_b32_e32 v2, v58, v175
	v_pk_mul_f32 v[58:59], v[38:39], v[38:39]
	v_ashrrev_i32_e32 v3, 31, v2
	v_add_f32_e32 v58, v59, v58
	ds_bpermute_b32 v59, v14, v58
	v_lshl_add_u64 v[2:3], v[2:3], 1, s[22:23]
	v_add_u32_e32 v62, 0x3c0, v61
	global_store_short v[2:3], v60, off sc1
	v_add_u32_e32 v2, v62, v174
	s_waitcnt lgkmcnt(0)
	v_add_f32_e32 v58, v58, v59
	ds_bpermute_b32 v59, v10, v58
	v_ashrrev_i32_e32 v3, 31, v2
	v_lshl_add_u64 v[2:3], v[2:3], 1, s[22:23]
	global_store_short v[2:3], v15, off sc1
	v_add_u32_e32 v2, v62, v175
	s_waitcnt lgkmcnt(0)
	v_add_f32_e32 v58, v58, v59
	ds_bpermute_b32 v59, v11, v58
	v_ashrrev_i32_e32 v3, 31, v2
	v_lshl_add_u64 v[2:3], v[2:3], 1, s[22:23]
	v_add_u32_e32 v62, 0x480, v61
	global_store_short v[2:3], v60, off sc1
	s_waitcnt lgkmcnt(0)
	v_add_f32_e32 v58, v58, v59
	ds_bpermute_b32 v59, v12, v58
	v_add_u32_e32 v2, v62, v174
	v_ashrrev_i32_e32 v3, 31, v2
	v_lshl_add_u64 v[2:3], v[2:3], 1, s[22:23]
	global_store_short v[2:3], v15, off sc1
	v_add_u32_e32 v2, v62, v175
	s_waitcnt lgkmcnt(0)
	v_add_f32_e32 v58, v58, v59
	v_ashrrev_i32_e32 v3, 31, v2
	ds_bpermute_b32 v59, v13, v58
	v_lshl_add_u64 v[2:3], v[2:3], 1, s[22:23]
	v_add_u32_e32 v61, 0x540, v61
	global_store_short v[2:3], v60, off sc1
	v_or_b32_e32 v2, v61, v174
	v_ashrrev_i32_e32 v3, 31, v2
	v_lshl_add_u64 v[2:3], v[2:3], 1, s[22:23]
	global_store_short v[2:3], v15, off sc1
	s_waitcnt lgkmcnt(0)
	v_add_f32_e32 v3, v58, v59
	v_fmamk_f32 v3, v3, 0x3c800000, v209
	v_rsq_f32_e32 v58, v3
	v_or_b32_e32 v2, v61, v175
	v_ashrrev_i32_e32 v3, 31, v2
	v_lshl_add_u64 v[2:3], v[2:3], 1, s[22:23]
	global_store_short v[2:3], v60, off sc1
	v_pk_mul_f32 v[2:3], v[0:1], v[58:59] op_sel_hi:[1,0]
	s_and_b64 vcc, exec, s[4:5]
	v_pk_mul_f32 v[2:3], v[38:39], v[2:3]
	s_mov_b64 s[80:81], -1
	s_cbranch_vccnz .LBB0_318
	v_add_u32_e32 v15, s76, v187
	v_lshl_or_b32 v58, v15, 6, v156
	v_ashrrev_i32_e32 v59, 31, v58
	v_lshl_add_u64 v[58:59], v[58:59], 2, s[24:25]
	s_mov_b64 s[80:81], 0
	global_store_dword v[58:59], v3, off sc1
	global_store_dword v[58:59], v2, off offset:128 sc1

.LBB0_320:
	v_cvt_pk_bf16_f32 v60, v2, s0
	v_add_u32_e32 v2, s11, v187
	v_mul_lo_u32 v61, v2, s94
	v_or_b32_e32 v2, v61, v174
	v_cvt_pk_bf16_f32 v15, v3, s0
	v_ashrrev_i32_e32 v3, 31, v2
	v_lshl_add_u64 v[2:3], v[2:3], 1, s[22:23]
	global_store_short v[2:3], v15, off sc1
	v_or_b32_e32 v2, v61, v175
	v_ashrrev_i32_e32 v3, 31, v2
	v_lshl_add_u64 v[2:3], v[2:3], 1, s[22:23]
	v_or_b32_e32 v58, 0xc0, v61
	global_store_short v[2:3], v60, off sc1
	v_add_u32_e32 v2, v58, v174
	v_ashrrev_i32_e32 v3, 31, v2
	v_lshl_add_u64 v[2:3], v[2:3], 1, s[22:23]
	global_store_short v[2:3], v15, off sc1
	v_add_u32_e32 v2, v58, v175
	v_ashrrev_i32_e32 v3, 31, v2
	v_lshl_add_u64 v[2:3], v[2:3], 1, s[22:23]
	v_or_b32_e32 v58, 0x180, v61
	global_store_short v[2:3], v60, off sc1
	v_add_u32_e32 v2, v58, v174
	v_ashrrev_i32_e32 v3, 31, v2
	v_lshl_add_u64 v[2:3], v[2:3], 1, s[22:23]
	global_store_short v[2:3], v15, off sc1
	v_add_u32_e32 v2, v58, v175
	v_ashrrev_i32_e32 v3, 31, v2
	v_lshl_add_u64 v[2:3], v[2:3], 1, s[22:23]
	v_add_u32_e32 v58, 0x240, v61
	global_store_short v[2:3], v60, off sc1
	v_or_b32_e32 v2, v58, v174
	v_ashrrev_i32_e32 v3, 31, v2
	v_lshl_add_u64 v[2:3], v[2:3], 1, s[22:23]
	global_store_short v[2:3], v15, off sc1
	v_or_b32_e32 v2, v58, v175
	v_ashrrev_i32_e32 v3, 31, v2
	v_lshl_add_u64 v[2:3], v[2:3], 1, s[22:23]
	v_add_u32_e32 v58, 0x300, v61
	global_store_short v[2:3], v60, off sc1
	v_or_b32_e32 v2, v58, v174
	v_ashrrev_i32_e32 v3, 31, v2
	v_lshl_add_u64 v[2:3], v[2:3], 1, s[22:23]
	global_store_short v[2:3], v15, off sc1
	v_or_b32_e32 v2, v58, v175
	v_pk_mul_f32 v[58:59], v[36:37], v[36:37]
	v_ashrrev_i32_e32 v3, 31, v2
	v_add_f32_e32 v58, v59, v58
	ds_bpermute_b32 v59, v14, v58
	v_lshl_add_u64 v[2:3], v[2:3], 1, s[22:23]
	v_add_u32_e32 v62, 0x3c0, v61
	global_store_short v[2:3], v60, off sc1
	v_add_u32_e32 v2, v62, v174
	s_waitcnt lgkmcnt(0)
	v_add_f32_e32 v58, v58, v59
	ds_bpermute_b32 v59, v10, v58
	v_ashrrev_i32_e32 v3, 31, v2
	v_lshl_add_u64 v[2:3], v[2:3], 1, s[22:23]
	global_store_short v[2:3], v15, off sc1
	v_add_u32_e32 v2, v62, v175
	s_waitcnt lgkmcnt(0)
	v_add_f32_e32 v58, v58, v59
	ds_bpermute_b32 v59, v11, v58
	v_ashrrev_i32_e32 v3, 31, v2
	v_lshl_add_u64 v[2:3], v[2:3], 1, s[22:23]
	v_add_u32_e32 v62, 0x480, v61
	global_store_short v[2:3], v60, off sc1
	s_waitcnt lgkmcnt(0)
	v_add_f32_e32 v58, v58, v59
	ds_bpermute_b32 v59, v12, v58
	v_add_u32_e32 v2, v62, v174
	v_ashrrev_i32_e32 v3, 31, v2
	v_lshl_add_u64 v[2:3], v[2:3], 1, s[22:23]
	global_store_short v[2:3], v15, off sc1
	v_add_u32_e32 v2, v62, v175
	s_waitcnt lgkmcnt(0)
	v_add_f32_e32 v58, v58, v59
	v_ashrrev_i32_e32 v3, 31, v2
	ds_bpermute_b32 v59, v13, v58
	v_lshl_add_u64 v[2:3], v[2:3], 1, s[22:23]
	v_add_u32_e32 v61, 0x540, v61
	global_store_short v[2:3], v60, off sc1
	v_or_b32_e32 v2, v61, v174
	v_ashrrev_i32_e32 v3, 31, v2
	v_lshl_add_u64 v[2:3], v[2:3], 1, s[22:23]
	global_store_short v[2:3], v15, off sc1
	s_waitcnt lgkmcnt(0)
	v_add_f32_e32 v3, v58, v59
	v_fmamk_f32 v3, v3, 0x3c800000, v209
	v_rsq_f32_e32 v58, v3
	v_or_b32_e32 v2, v61, v175
	v_ashrrev_i32_e32 v3, 31, v2
	v_lshl_add_u64 v[2:3], v[2:3], 1, s[22:23]
	global_store_short v[2:3], v60, off sc1
	v_pk_mul_f32 v[2:3], v[0:1], v[58:59] op_sel_hi:[1,0]
	s_and_b64 vcc, exec, s[4:5]
	v_pk_mul_f32 v[2:3], v[36:37], v[2:3]
	s_mov_b64 s[80:81], -1
	s_cbranch_vccnz .LBB0_322
	v_add_u32_e32 v15, s76, v188
	v_lshl_or_b32 v58, v15, 6, v156
	v_ashrrev_i32_e32 v59, 31, v58
	v_lshl_add_u64 v[58:59], v[58:59], 2, s[24:25]
	s_mov_b64 s[80:81], 0
	global_store_dword v[58:59], v3, off sc1
	global_store_dword v[58:59], v2, off offset:128 sc1

.LBB0_324:
	v_cvt_pk_bf16_f32 v60, v2, s0
	v_add_u32_e32 v2, s11, v188
	v_mul_lo_u32 v61, v2, s94
	v_or_b32_e32 v2, v61, v174
	v_cvt_pk_bf16_f32 v15, v3, s0
	v_ashrrev_i32_e32 v3, 31, v2
	v_lshl_add_u64 v[2:3], v[2:3], 1, s[22:23]
	global_store_short v[2:3], v15, off sc1
	v_or_b32_e32 v2, v61, v175
	v_ashrrev_i32_e32 v3, 31, v2
	v_lshl_add_u64 v[2:3], v[2:3], 1, s[22:23]
	v_or_b32_e32 v58, 0xc0, v61
	global_store_short v[2:3], v60, off sc1
	v_add_u32_e32 v2, v58, v174
	v_ashrrev_i32_e32 v3, 31, v2
	v_lshl_add_u64 v[2:3], v[2:3], 1, s[22:23]
	global_store_short v[2:3], v15, off sc1
	v_add_u32_e32 v2, v58, v175
	v_ashrrev_i32_e32 v3, 31, v2
	v_lshl_add_u64 v[2:3], v[2:3], 1, s[22:23]
	v_or_b32_e32 v58, 0x180, v61
	global_store_short v[2:3], v60, off sc1
	v_add_u32_e32 v2, v58, v174
	v_ashrrev_i32_e32 v3, 31, v2
	v_lshl_add_u64 v[2:3], v[2:3], 1, s[22:23]
	global_store_short v[2:3], v15, off sc1
	v_add_u32_e32 v2, v58, v175
	v_ashrrev_i32_e32 v3, 31, v2
	v_lshl_add_u64 v[2:3], v[2:3], 1, s[22:23]
	v_add_u32_e32 v58, 0x240, v61
	global_store_short v[2:3], v60, off sc1
	v_or_b32_e32 v2, v58, v174
	v_ashrrev_i32_e32 v3, 31, v2
	v_lshl_add_u64 v[2:3], v[2:3], 1, s[22:23]
	global_store_short v[2:3], v15, off sc1
	v_or_b32_e32 v2, v58, v175
	v_ashrrev_i32_e32 v3, 31, v2
	v_lshl_add_u64 v[2:3], v[2:3], 1, s[22:23]
	v_add_u32_e32 v58, 0x300, v61
	global_store_short v[2:3], v60, off sc1
	v_or_b32_e32 v2, v58, v174
	v_ashrrev_i32_e32 v3, 31, v2
	v_lshl_add_u64 v[2:3], v[2:3], 1, s[22:23]
	global_store_short v[2:3], v15, off sc1
	v_or_b32_e32 v2, v58, v175
	v_pk_mul_f32 v[58:59], v[34:35], v[34:35]
	v_ashrrev_i32_e32 v3, 31, v2
	v_add_f32_e32 v58, v59, v58
	ds_bpermute_b32 v59, v14, v58
	v_lshl_add_u64 v[2:3], v[2:3], 1, s[22:23]
	v_add_u32_e32 v62, 0x3c0, v61
	global_store_short v[2:3], v60, off sc1
	v_add_u32_e32 v2, v62, v174
	s_waitcnt lgkmcnt(0)
	v_add_f32_e32 v58, v58, v59
	ds_bpermute_b32 v59, v10, v58
	v_ashrrev_i32_e32 v3, 31, v2
	v_lshl_add_u64 v[2:3], v[2:3], 1, s[22:23]
	global_store_short v[2:3], v15, off sc1
	v_add_u32_e32 v2, v62, v175
	s_waitcnt lgkmcnt(0)
	v_add_f32_e32 v58, v58, v59
	ds_bpermute_b32 v59, v11, v58
	v_ashrrev_i32_e32 v3, 31, v2
	v_lshl_add_u64 v[2:3], v[2:3], 1, s[22:23]
	v_add_u32_e32 v62, 0x480, v61
	global_store_short v[2:3], v60, off sc1
	s_waitcnt lgkmcnt(0)
	v_add_f32_e32 v58, v58, v59
	ds_bpermute_b32 v59, v12, v58
	v_add_u32_e32 v2, v62, v174
	v_ashrrev_i32_e32 v3, 31, v2
	v_lshl_add_u64 v[2:3], v[2:3], 1, s[22:23]
	global_store_short v[2:3], v15, off sc1
	v_add_u32_e32 v2, v62, v175
	s_waitcnt lgkmcnt(0)
	v_add_f32_e32 v58, v58, v59
	v_ashrrev_i32_e32 v3, 31, v2
	ds_bpermute_b32 v59, v13, v58
	v_lshl_add_u64 v[2:3], v[2:3], 1, s[22:23]
	v_add_u32_e32 v61, 0x540, v61
	global_store_short v[2:3], v60, off sc1
	v_or_b32_e32 v2, v61, v174
	v_ashrrev_i32_e32 v3, 31, v2
	v_lshl_add_u64 v[2:3], v[2:3], 1, s[22:23]
	global_store_short v[2:3], v15, off sc1
	s_waitcnt lgkmcnt(0)
	v_add_f32_e32 v3, v58, v59
	v_fmamk_f32 v3, v3, 0x3c800000, v209
	v_rsq_f32_e32 v58, v3
	v_or_b32_e32 v2, v61, v175
	v_ashrrev_i32_e32 v3, 31, v2
	v_lshl_add_u64 v[2:3], v[2:3], 1, s[22:23]
	global_store_short v[2:3], v60, off sc1
	v_pk_mul_f32 v[2:3], v[0:1], v[58:59] op_sel_hi:[1,0]
	s_and_b64 vcc, exec, s[4:5]
	v_pk_mul_f32 v[2:3], v[34:35], v[2:3]
	s_mov_b64 s[80:81], -1
	s_cbranch_vccnz .LBB0_326
	v_add_u32_e32 v15, s76, v189
	v_lshl_or_b32 v58, v15, 6, v156
	v_ashrrev_i32_e32 v59, 31, v58
	v_lshl_add_u64 v[58:59], v[58:59], 2, s[24:25]
	s_mov_b64 s[80:81], 0
	global_store_dword v[58:59], v3, off sc1
	global_store_dword v[58:59], v2, off offset:128 sc1

.LBB0_328:
	v_cvt_pk_bf16_f32 v60, v2, s0
	v_add_u32_e32 v2, s11, v189
	v_mul_lo_u32 v61, v2, s94
	v_or_b32_e32 v2, v61, v174
	v_cvt_pk_bf16_f32 v15, v3, s0
	v_ashrrev_i32_e32 v3, 31, v2
	v_lshl_add_u64 v[2:3], v[2:3], 1, s[22:23]
	global_store_short v[2:3], v15, off sc1
	v_or_b32_e32 v2, v61, v175
	v_ashrrev_i32_e32 v3, 31, v2
	v_lshl_add_u64 v[2:3], v[2:3], 1, s[22:23]
	v_or_b32_e32 v58, 0xc0, v61
	global_store_short v[2:3], v60, off sc1
	v_add_u32_e32 v2, v58, v174
	v_ashrrev_i32_e32 v3, 31, v2
	v_lshl_add_u64 v[2:3], v[2:3], 1, s[22:23]
	global_store_short v[2:3], v15, off sc1
	v_add_u32_e32 v2, v58, v175
	v_ashrrev_i32_e32 v3, 31, v2
	v_lshl_add_u64 v[2:3], v[2:3], 1, s[22:23]
	v_or_b32_e32 v58, 0x180, v61
	global_store_short v[2:3], v60, off sc1
	v_add_u32_e32 v2, v58, v174
	v_ashrrev_i32_e32 v3, 31, v2
	v_lshl_add_u64 v[2:3], v[2:3], 1, s[22:23]
	global_store_short v[2:3], v15, off sc1
	v_add_u32_e32 v2, v58, v175
	v_ashrrev_i32_e32 v3, 31, v2
	v_lshl_add_u64 v[2:3], v[2:3], 1, s[22:23]
	v_add_u32_e32 v58, 0x240, v61
	global_store_short v[2:3], v60, off sc1
	v_or_b32_e32 v2, v58, v174
	v_ashrrev_i32_e32 v3, 31, v2
	v_lshl_add_u64 v[2:3], v[2:3], 1, s[22:23]
	global_store_short v[2:3], v15, off sc1
	v_or_b32_e32 v2, v58, v175
	v_ashrrev_i32_e32 v3, 31, v2
	v_lshl_add_u64 v[2:3], v[2:3], 1, s[22:23]
	v_add_u32_e32 v58, 0x300, v61
	global_store_short v[2:3], v60, off sc1
	v_or_b32_e32 v2, v58, v174
	v_ashrrev_i32_e32 v3, 31, v2
	v_lshl_add_u64 v[2:3], v[2:3], 1, s[22:23]
	global_store_short v[2:3], v15, off sc1
	v_or_b32_e32 v2, v58, v175
	v_pk_mul_f32 v[58:59], v[32:33], v[32:33]
	v_ashrrev_i32_e32 v3, 31, v2
	v_add_f32_e32 v58, v59, v58
	ds_bpermute_b32 v14, v14, v58
	v_lshl_add_u64 v[2:3], v[2:3], 1, s[22:23]
	v_add_u32_e32 v62, 0x3c0, v61
	global_store_short v[2:3], v60, off sc1
	v_add_u32_e32 v2, v62, v174
	s_waitcnt lgkmcnt(0)
	v_add_f32_e32 v14, v58, v14
	ds_bpermute_b32 v10, v10, v14
	v_ashrrev_i32_e32 v3, 31, v2
	v_lshl_add_u64 v[2:3], v[2:3], 1, s[22:23]
	global_store_short v[2:3], v15, off sc1
	v_add_u32_e32 v2, v62, v175
	s_waitcnt lgkmcnt(0)
	v_add_f32_e32 v10, v14, v10
	ds_bpermute_b32 v11, v11, v10
	v_ashrrev_i32_e32 v3, 31, v2
	v_lshl_add_u64 v[2:3], v[2:3], 1, s[22:23]
	v_add_u32_e32 v58, 0x480, v61
	global_store_short v[2:3], v60, off sc1
	s_waitcnt lgkmcnt(0)
	v_add_f32_e32 v10, v10, v11
	ds_bpermute_b32 v11, v12, v10
	v_add_u32_e32 v2, v58, v174
	v_ashrrev_i32_e32 v3, 31, v2
	v_lshl_add_u64 v[2:3], v[2:3], 1, s[22:23]
	global_store_short v[2:3], v15, off sc1
	v_add_u32_e32 v2, v58, v175
	s_waitcnt lgkmcnt(0)
	v_add_f32_e32 v10, v10, v11
	v_ashrrev_i32_e32 v3, 31, v2
	ds_bpermute_b32 v11, v13, v10
	v_lshl_add_u64 v[2:3], v[2:3], 1, s[22:23]
	v_add_u32_e32 v12, 0x540, v61
	global_store_short v[2:3], v60, off sc1
	v_or_b32_e32 v2, v12, v174
	v_ashrrev_i32_e32 v3, 31, v2
	v_lshl_add_u64 v[2:3], v[2:3], 1, s[22:23]
	global_store_short v[2:3], v15, off sc1
	s_waitcnt lgkmcnt(0)
	v_add_f32_e32 v3, v10, v11
	v_fmamk_f32 v3, v3, 0x3c800000, v209
	v_rsq_f32_e32 v10, v3
	v_or_b32_e32 v2, v12, v175
	v_ashrrev_i32_e32 v3, 31, v2
	v_lshl_add_u64 v[2:3], v[2:3], 1, s[22:23]
	v_pk_mul_f32 v[0:1], v[0:1], v[10:11] op_sel_hi:[1,0]
	s_and_b64 vcc, exec, s[4:5]
	v_pk_mul_f32 v[0:1], v[32:33], v[0:1]
	s_mov_b64 s[80:81], -1
	global_store_short v[2:3], v60, off sc1
	s_cbranch_vccnz .LBB0_330
	v_add_u32_e32 v2, s76, v190
	v_lshl_or_b32 v2, v2, 6, v156
	v_ashrrev_i32_e32 v3, 31, v2
	v_lshl_add_u64 v[2:3], v[2:3], 2, s[24:25]
	s_mov_b64 s[80:81], 0
	global_store_dword v[2:3], v1, off sc1
	global_store_dword v[2:3], v0, off offset:128 sc1

.LBB0_332:
	v_cvt_pk_bf16_f32 v3, v0, s0
	v_add_u32_e32 v0, s11, v190
	v_mul_lo_u32 v10, v0, s94
	v_or_b32_e32 v0, v10, v174
	v_cvt_pk_bf16_f32 v2, v1, s0
	v_ashrrev_i32_e32 v1, 31, v0
	v_lshl_add_u64 v[0:1], v[0:1], 1, s[22:23]
	global_store_short v[0:1], v2, off sc1
	v_or_b32_e32 v0, v10, v175
	v_ashrrev_i32_e32 v1, 31, v0
	v_lshl_add_u64 v[0:1], v[0:1], 1, s[22:23]
	v_or_b32_e32 v11, 0xc0, v10
	global_store_short v[0:1], v3, off sc1
	v_add_u32_e32 v0, v11, v174
	v_ashrrev_i32_e32 v1, 31, v0
	v_lshl_add_u64 v[0:1], v[0:1], 1, s[22:23]
	global_store_short v[0:1], v2, off sc1
	v_add_u32_e32 v0, v11, v175
	v_ashrrev_i32_e32 v1, 31, v0
	v_lshl_add_u64 v[0:1], v[0:1], 1, s[22:23]
	v_or_b32_e32 v11, 0x180, v10
	global_store_short v[0:1], v3, off sc1
	v_add_u32_e32 v0, v11, v174
	v_ashrrev_i32_e32 v1, 31, v0
	v_lshl_add_u64 v[0:1], v[0:1], 1, s[22:23]
	global_store_short v[0:1], v2, off sc1
	v_add_u32_e32 v0, v11, v175
	v_ashrrev_i32_e32 v1, 31, v0
	v_lshl_add_u64 v[0:1], v[0:1], 1, s[22:23]
	v_add_u32_e32 v11, 0x240, v10
	global_store_short v[0:1], v3, off sc1
	v_or_b32_e32 v0, v11, v174
	v_ashrrev_i32_e32 v1, 31, v0
	v_lshl_add_u64 v[0:1], v[0:1], 1, s[22:23]
	global_store_short v[0:1], v2, off sc1
	v_or_b32_e32 v0, v11, v175
	v_ashrrev_i32_e32 v1, 31, v0
	v_lshl_add_u64 v[0:1], v[0:1], 1, s[22:23]
	v_add_u32_e32 v11, 0x300, v10
	global_store_short v[0:1], v3, off sc1
	v_or_b32_e32 v0, v11, v174
	v_ashrrev_i32_e32 v1, 31, v0
	v_lshl_add_u64 v[0:1], v[0:1], 1, s[22:23]
	global_store_short v[0:1], v2, off sc1
	v_or_b32_e32 v0, v11, v175
	v_ashrrev_i32_e32 v1, 31, v0
	v_lshl_add_u64 v[0:1], v[0:1], 1, s[22:23]
	v_add_u32_e32 v11, 0x3c0, v10
	global_store_short v[0:1], v3, off sc1
	v_add_u32_e32 v0, v11, v174
	v_ashrrev_i32_e32 v1, 31, v0
	v_lshl_add_u64 v[0:1], v[0:1], 1, s[22:23]
	global_store_short v[0:1], v2, off sc1
	v_add_u32_e32 v0, v11, v175
	v_ashrrev_i32_e32 v1, 31, v0
	v_lshl_add_u64 v[0:1], v[0:1], 1, s[22:23]
	v_add_u32_e32 v11, 0x480, v10
	global_store_short v[0:1], v3, off sc1
	v_add_u32_e32 v0, v11, v174
	v_ashrrev_i32_e32 v1, 31, v0
	v_lshl_add_u64 v[0:1], v[0:1], 1, s[22:23]
	global_store_short v[0:1], v2, off sc1
	v_add_u32_e32 v0, v11, v175
	v_ashrrev_i32_e32 v1, 31, v0
	v_lshl_add_u64 v[0:1], v[0:1], 1, s[22:23]
	v_add_u32_e32 v10, 0x540, v10
	global_store_short v[0:1], v3, off sc1
	v_or_b32_e32 v0, v10, v174
	v_ashrrev_i32_e32 v1, 31, v0
	v_lshl_add_u64 v[0:1], v[0:1], 1, s[22:23]
	global_store_short v[0:1], v2, off sc1
	v_or_b32_e32 v0, v10, v175
	v_ashrrev_i32_e32 v1, 31, v0
	v_lshl_add_u64 v[0:1], v[0:1], 1, s[22:23]
	global_store_short v[0:1], v3, off sc1
	s_mov_b64 s[80:81], 0
.LBB0_333:
	s_and_b64 vcc, exec, s[80:81]
	s_cbranch_vccz .LBB0_495
	v_mov_b32_e32 v0, s96
	ds_read_b64 v[0:1], v0
	v_lshl_add_u64 v[2:3], s[78:79], 0, v[156:157]
	v_add_lshl_u32 v10, s11, v173, 8
	s_and_b64 vcc, exec, s[4:5]
	s_waitcnt lgkmcnt(0)
	v_readfirstlane_b32 s8, v0
	v_readfirstlane_b32 s77, v1
	s_nop 0
	v_mov_b32_e32 v0, s8
	v_mov_b32_e32 v1, s77
	v_lshl_add_u64 v[0:1], v[2:3], 2, v[0:1]
	global_load_dword v96, v[0:1], off offset:-1536
	v_add_u32_e32 v3, s78, v166
	v_add_u32_e32 v12, v10, v3
	v_ashrrev_i32_e32 v13, 31, v12
	v_lshl_add_u64 v[12:13], v[12:13], 1, s[26:27]
	s_waitcnt vmcnt(0)
	v_mul_f32_e32 v2, v79, v96
	v_cvt_pk_bf16_f32 v11, v2, s0
	global_store_short v[12:13], v11, off sc1
	s_cbranch_vccnz .LBB0_336
	v_lshl_add_u32 v12, v164, 8, v3
	v_ashrrev_i32_e32 v13, 31, v12
	v_lshl_add_u64 v[12:13], v[12:13], 2, s[28:29]
	global_store_dword v[12:13], v2, off sc1
.LBB0_336:
	v_add_lshl_u32 v13, s11, v176, 8
	v_add_u32_e32 v14, v13, v3
	v_mul_f32_e32 v11, v75, v96
	v_ashrrev_i32_e32 v15, 31, v14
	v_cvt_pk_bf16_f32 v2, v11, s0
	v_lshl_add_u64 v[14:15], v[14:15], 1, s[26:27]
	global_store_short v[14:15], v2, off sc1
	s_and_b64 vcc, exec, s[4:5]
	v_add_u32_e32 v2, s76, v176
	s_cbranch_vccnz .LBB0_338
	v_lshl_add_u32 v14, v2, 8, v3
	v_ashrrev_i32_e32 v15, 31, v14
	v_lshl_add_u64 v[14:15], v[14:15], 2, s[28:29]
	global_store_dword v[14:15], v11, off sc1
.LBB0_338:
	v_add_lshl_u32 v15, s11, v177, 8
	v_add_u32_e32 v58, v15, v3
	v_mul_f32_e32 v12, v73, v96
	v_ashrrev_i32_e32 v59, 31, v58
	v_cvt_pk_bf16_f32 v11, v12, s0
	v_lshl_add_u64 v[58:59], v[58:59], 1, s[26:27]
	global_store_short v[58:59], v11, off sc1
	s_and_b64 vcc, exec, s[4:5]
	v_add_u32_e32 v11, s76, v177
	s_cbranch_vccnz .LBB0_340
	v_lshl_add_u32 v58, v11, 8, v3
	v_ashrrev_i32_e32 v59, 31, v58
	v_lshl_add_u64 v[58:59], v[58:59], 2, s[28:29]
	global_store_dword v[58:59], v12, off sc1
.LBB0_340:
	v_add_lshl_u32 v59, s11, v178, 8
	v_add_u32_e32 v60, v59, v3
	v_mul_f32_e32 v14, v71, v96
	v_ashrrev_i32_e32 v61, 31, v60
	v_cvt_pk_bf16_f32 v12, v14, s0
	v_lshl_add_u64 v[60:61], v[60:61], 1, s[26:27]
	global_store_short v[60:61], v12, off sc1
	s_and_b64 vcc, exec, s[4:5]
	v_add_u32_e32 v12, s76, v178
	s_cbranch_vccnz .LBB0_342
	v_lshl_add_u32 v60, v12, 8, v3
	v_ashrrev_i32_e32 v61, 31, v60
	v_lshl_add_u64 v[60:61], v[60:61], 2, s[28:29]
	global_store_dword v[60:61], v14, off sc1
.LBB0_342:
	v_add_lshl_u32 v61, s11, v179, 8
	v_add_u32_e32 v62, v61, v3
	v_mul_f32_e32 v58, v69, v96
	v_ashrrev_i32_e32 v63, 31, v62
	v_cvt_pk_bf16_f32 v14, v58, s0
	v_lshl_add_u64 v[62:63], v[62:63], 1, s[26:27]
	global_store_short v[62:63], v14, off sc1
	s_and_b64 vcc, exec, s[4:5]
	v_add_u32_e32 v14, s76, v179
	s_cbranch_vccnz .LBB0_344
	v_lshl_add_u32 v62, v14, 8, v3
	v_ashrrev_i32_e32 v63, 31, v62
	v_lshl_add_u64 v[62:63], v[62:63], 2, s[28:29]
	global_store_dword v[62:63], v58, off sc1
.LBB0_344:
	v_add_lshl_u32 v63, s11, v180, 8
	v_add_u32_e32 v80, v63, v3
	v_mul_f32_e32 v60, v67, v96
	v_ashrrev_i32_e32 v81, 31, v80
	v_cvt_pk_bf16_f32 v58, v60, s0
	v_lshl_add_u64 v[80:81], v[80:81], 1, s[26:27]
	global_store_short v[80:81], v58, off sc1
	s_and_b64 vcc, exec, s[4:5]
	v_add_u32_e32 v58, s76, v180
	s_cbranch_vccnz .LBB0_346
	v_lshl_add_u32 v80, v58, 8, v3
	v_ashrrev_i32_e32 v81, 31, v80
	v_lshl_add_u64 v[80:81], v[80:81], 2, s[28:29]
	global_store_dword v[80:81], v60, off sc1
.LBB0_346:
	v_add_lshl_u32 v81, s11, v181, 8
	v_add_u32_e32 v84, v81, v3
	v_mul_f32_e32 v62, v65, v96
	v_ashrrev_i32_e32 v85, 31, v84
	v_cvt_pk_bf16_f32 v60, v62, s0
	v_lshl_add_u64 v[84:85], v[84:85], 1, s[26:27]
	global_store_short v[84:85], v60, off sc1
	s_and_b64 vcc, exec, s[4:5]
	v_add_u32_e32 v60, s76, v181
	s_cbranch_vccnz .LBB0_348
	v_lshl_add_u32 v84, v60, 8, v3
	v_ashrrev_i32_e32 v85, 31, v84
	v_lshl_add_u64 v[84:85], v[84:85], 2, s[28:29]
	global_store_dword v[84:85], v62, off sc1
.LBB0_348:
	v_add_lshl_u32 v85, s11, v182, 8
	v_add_u32_e32 v86, v85, v3
	v_mul_f32_e32 v80, v55, v96
	v_ashrrev_i32_e32 v87, 31, v86
	v_cvt_pk_bf16_f32 v62, v80, s0
	v_lshl_add_u64 v[86:87], v[86:87], 1, s[26:27]
	global_store_short v[86:87], v62, off sc1
	s_and_b64 vcc, exec, s[4:5]
	v_add_u32_e32 v62, s76, v182
	s_cbranch_vccnz .LBB0_350
	v_lshl_add_u32 v86, v62, 8, v3
	v_ashrrev_i32_e32 v87, 31, v86
	v_lshl_add_u64 v[86:87], v[86:87], 2, s[28:29]
	global_store_dword v[86:87], v80, off sc1
.LBB0_350:
	v_add_lshl_u32 v87, s11, v183, 8
	v_add_u32_e32 v88, v87, v3
	v_mul_f32_e32 v84, v53, v96
	v_ashrrev_i32_e32 v89, 31, v88
	v_cvt_pk_bf16_f32 v80, v84, s0
	v_lshl_add_u64 v[88:89], v[88:89], 1, s[26:27]
	global_store_short v[88:89], v80, off sc1
	s_and_b64 vcc, exec, s[4:5]
	v_add_u32_e32 v80, s76, v183
	s_cbranch_vccnz .LBB0_352
	v_lshl_add_u32 v88, v80, 8, v3
	v_ashrrev_i32_e32 v89, 31, v88
	v_lshl_add_u64 v[88:89], v[88:89], 2, s[28:29]
	global_store_dword v[88:89], v84, off sc1
.LBB0_352:
	v_add_lshl_u32 v89, s11, v184, 8
	v_add_u32_e32 v90, v89, v3
	v_mul_f32_e32 v86, v51, v96
	v_ashrrev_i32_e32 v91, 31, v90
	v_cvt_pk_bf16_f32 v84, v86, s0
	v_lshl_add_u64 v[90:91], v[90:91], 1, s[26:27]
	global_store_short v[90:91], v84, off sc1
	s_and_b64 vcc, exec, s[4:5]
	v_add_u32_e32 v84, s76, v184
	s_cbranch_vccnz .LBB0_354
	v_lshl_add_u32 v90, v84, 8, v3
	v_ashrrev_i32_e32 v91, 31, v90
	v_lshl_add_u64 v[90:91], v[90:91], 2, s[28:29]
	global_store_dword v[90:91], v86, off sc1
.LBB0_354:
	v_add_lshl_u32 v91, s11, v185, 8
	v_add_u32_e32 v92, v91, v3
	v_mul_f32_e32 v88, v49, v96
	v_ashrrev_i32_e32 v93, 31, v92
	v_cvt_pk_bf16_f32 v86, v88, s0
	v_lshl_add_u64 v[92:93], v[92:93], 1, s[26:27]
	global_store_short v[92:93], v86, off sc1
	s_and_b64 vcc, exec, s[4:5]
	v_add_u32_e32 v86, s76, v185
	s_cbranch_vccnz .LBB0_356
	v_lshl_add_u32 v92, v86, 8, v3
	v_ashrrev_i32_e32 v93, 31, v92
	v_lshl_add_u64 v[92:93], v[92:93], 2, s[28:29]
	global_store_dword v[92:93], v88, off sc1
.LBB0_356:
	v_add_lshl_u32 v93, s11, v186, 8
	v_add_u32_e32 v94, v93, v3
	v_mul_f32_e32 v90, v41, v96
	v_ashrrev_i32_e32 v95, 31, v94
	v_cvt_pk_bf16_f32 v88, v90, s0
	v_lshl_add_u64 v[94:95], v[94:95], 1, s[26:27]
	global_store_short v[94:95], v88, off sc1
	s_and_b64 vcc, exec, s[4:5]
	v_add_u32_e32 v88, s76, v186
	s_cbranch_vccnz .LBB0_358
	v_lshl_add_u32 v94, v88, 8, v3
	v_ashrrev_i32_e32 v95, 31, v94
	v_lshl_add_u64 v[94:95], v[94:95], 2, s[28:29]
	global_store_dword v[94:95], v90, off sc1
.LBB0_358:
	v_add_lshl_u32 v95, s11, v187, 8
	v_add_u32_e32 v98, v95, v3
	v_mul_f32_e32 v92, v39, v96
	v_ashrrev_i32_e32 v99, 31, v98
	v_cvt_pk_bf16_f32 v90, v92, s0
	v_lshl_add_u64 v[98:99], v[98:99], 1, s[26:27]
	global_store_short v[98:99], v90, off sc1
	s_and_b64 vcc, exec, s[4:5]
	v_add_u32_e32 v90, s76, v187
	s_cbranch_vccnz .LBB0_360
	v_lshl_add_u32 v98, v90, 8, v3
	v_ashrrev_i32_e32 v99, 31, v98
	v_lshl_add_u64 v[98:99], v[98:99], 2, s[28:29]
	global_store_dword v[98:99], v92, off sc1
.LBB0_360:
	v_add_lshl_u32 v97, s11, v188, 8
	v_add_u32_e32 v98, v97, v3
	v_mul_f32_e32 v94, v37, v96
	v_ashrrev_i32_e32 v99, 31, v98
	v_cvt_pk_bf16_f32 v92, v94, s0
	v_lshl_add_u64 v[98:99], v[98:99], 1, s[26:27]
	global_store_short v[98:99], v92, off sc1
	s_and_b64 vcc, exec, s[4:5]
	v_add_u32_e32 v92, s76, v188
	s_cbranch_vccnz .LBB0_362
	v_lshl_add_u32 v98, v92, 8, v3
	v_ashrrev_i32_e32 v99, 31, v98
	v_lshl_add_u64 v[98:99], v[98:99], 2, s[28:29]
	global_store_dword v[98:99], v94, off sc1
.LBB0_362:
	v_add_lshl_u32 v98, s11, v189, 8
	v_add_u32_e32 v100, v98, v3
	v_mul_f32_e32 v99, v35, v96
	v_ashrrev_i32_e32 v101, 31, v100
	v_cvt_pk_bf16_f32 v94, v99, s0
	v_lshl_add_u64 v[100:101], v[100:101], 1, s[26:27]
	global_store_short v[100:101], v94, off sc1
	s_and_b64 vcc, exec, s[4:5]
	v_add_u32_e32 v94, s76, v189
	s_cbranch_vccnz .LBB0_364
	v_lshl_add_u32 v100, v94, 8, v3
	v_ashrrev_i32_e32 v101, 31, v100
	v_lshl_add_u64 v[100:101], v[100:101], 2, s[28:29]
	global_store_dword v[100:101], v99, off sc1
.LBB0_364:
	v_add_lshl_u32 v99, s11, v190, 8
	v_add_u32_e32 v102, v99, v3
	v_mul_f32_e32 v100, v33, v96
	v_ashrrev_i32_e32 v103, 31, v102
	v_cvt_pk_bf16_f32 v96, v100, s0
	v_lshl_add_u64 v[102:103], v[102:103], 1, s[26:27]
	global_store_short v[102:103], v96, off sc1
	s_and_b64 vcc, exec, s[4:5]
	v_add_u32_e32 v96, s76, v190
	s_cbranch_vccnz .LBB0_366
	v_lshl_add_u32 v102, v96, 8, v3
	v_ashrrev_i32_e32 v103, 31, v102
	v_lshl_add_u64 v[102:103], v[102:103], 2, s[28:29]
	global_store_dword v[102:103], v100, off sc1
.LBB0_366:
	global_load_dword v101, v[0:1], off offset:-1408
	v_or_b32_e32 v100, 32, v3
	v_add_u32_e32 v102, v10, v100
	v_ashrrev_i32_e32 v103, 31, v102
	v_lshl_add_u64 v[104:105], v[102:103], 1, s[26:27]
	s_and_b64 vcc, exec, s[4:5]
	s_waitcnt vmcnt(0)
	v_mul_f32_e32 v102, v78, v101
	v_cvt_pk_bf16_f32 v103, v102, s0
	global_store_short v[104:105], v103, off sc1
	s_cbranch_vccnz .LBB0_368
	v_lshl_add_u32 v104, v164, 8, v100
	v_ashrrev_i32_e32 v105, 31, v104
	v_lshl_add_u64 v[104:105], v[104:105], 2, s[28:29]
	global_store_dword v[104:105], v102, off sc1
.LBB0_368:
	v_add_u32_e32 v104, v13, v100
	v_mul_f32_e32 v102, v74, v101
	v_ashrrev_i32_e32 v105, 31, v104
	v_cvt_pk_bf16_f32 v103, v102, s0
	v_lshl_add_u64 v[104:105], v[104:105], 1, s[26:27]
	s_and_b64 vcc, exec, s[4:5]
	global_store_short v[104:105], v103, off sc1
	s_cbranch_vccnz .LBB0_370
	v_lshl_add_u32 v104, v2, 8, v100
	v_ashrrev_i32_e32 v105, 31, v104
	v_lshl_add_u64 v[104:105], v[104:105], 2, s[28:29]
	global_store_dword v[104:105], v102, off sc1
.LBB0_370:
	v_add_u32_e32 v104, v15, v100
	v_mul_f32_e32 v102, v72, v101
	v_ashrrev_i32_e32 v105, 31, v104
	v_cvt_pk_bf16_f32 v103, v102, s0
	v_lshl_add_u64 v[104:105], v[104:105], 1, s[26:27]
	s_and_b64 vcc, exec, s[4:5]
	global_store_short v[104:105], v103, off sc1
	s_cbranch_vccnz .LBB0_372
	v_lshl_add_u32 v104, v11, 8, v100
	v_ashrrev_i32_e32 v105, 31, v104
	v_lshl_add_u64 v[104:105], v[104:105], 2, s[28:29]
	global_store_dword v[104:105], v102, off sc1
.LBB0_372:
	v_add_u32_e32 v104, v59, v100
	v_mul_f32_e32 v102, v70, v101
	v_ashrrev_i32_e32 v105, 31, v104
	v_cvt_pk_bf16_f32 v103, v102, s0
	v_lshl_add_u64 v[104:105], v[104:105], 1, s[26:27]
	s_and_b64 vcc, exec, s[4:5]
	global_store_short v[104:105], v103, off sc1
	s_cbranch_vccnz .LBB0_374
	v_lshl_add_u32 v104, v12, 8, v100
	v_ashrrev_i32_e32 v105, 31, v104
	v_lshl_add_u64 v[104:105], v[104:105], 2, s[28:29]
	global_store_dword v[104:105], v102, off sc1
.LBB0_374:
	v_add_u32_e32 v104, v61, v100
	v_mul_f32_e32 v102, v68, v101
	v_ashrrev_i32_e32 v105, 31, v104
	v_cvt_pk_bf16_f32 v103, v102, s0
	v_lshl_add_u64 v[104:105], v[104:105], 1, s[26:27]
	s_and_b64 vcc, exec, s[4:5]
	global_store_short v[104:105], v103, off sc1
	s_cbranch_vccnz .LBB0_376
	v_lshl_add_u32 v104, v14, 8, v100
	v_ashrrev_i32_e32 v105, 31, v104
	v_lshl_add_u64 v[104:105], v[104:105], 2, s[28:29]
	global_store_dword v[104:105], v102, off sc1
.LBB0_376:
	v_add_u32_e32 v104, v63, v100
	v_mul_f32_e32 v102, v66, v101
	v_ashrrev_i32_e32 v105, 31, v104
	v_cvt_pk_bf16_f32 v103, v102, s0
	v_lshl_add_u64 v[104:105], v[104:105], 1, s[26:27]
	s_and_b64 vcc, exec, s[4:5]
	global_store_short v[104:105], v103, off sc1
	s_cbranch_vccnz .LBB0_378
	v_lshl_add_u32 v104, v58, 8, v100
	v_ashrrev_i32_e32 v105, 31, v104
	v_lshl_add_u64 v[104:105], v[104:105], 2, s[28:29]
	global_store_dword v[104:105], v102, off sc1
.LBB0_378:
	v_add_u32_e32 v104, v81, v100
	v_mul_f32_e32 v102, v64, v101
	v_ashrrev_i32_e32 v105, 31, v104
	v_cvt_pk_bf16_f32 v103, v102, s0
	v_lshl_add_u64 v[104:105], v[104:105], 1, s[26:27]
	s_and_b64 vcc, exec, s[4:5]
	global_store_short v[104:105], v103, off sc1
	s_cbranch_vccnz .LBB0_380
	v_lshl_add_u32 v104, v60, 8, v100
	v_ashrrev_i32_e32 v105, 31, v104
	v_lshl_add_u64 v[104:105], v[104:105], 2, s[28:29]
	global_store_dword v[104:105], v102, off sc1
.LBB0_380:
	v_add_u32_e32 v104, v85, v100
	v_mul_f32_e32 v102, v54, v101
	v_ashrrev_i32_e32 v105, 31, v104
	v_cvt_pk_bf16_f32 v103, v102, s0
	v_lshl_add_u64 v[104:105], v[104:105], 1, s[26:27]
	s_and_b64 vcc, exec, s[4:5]
	global_store_short v[104:105], v103, off sc1
	s_cbranch_vccnz .LBB0_382
	v_lshl_add_u32 v104, v62, 8, v100
	v_ashrrev_i32_e32 v105, 31, v104
	v_lshl_add_u64 v[104:105], v[104:105], 2, s[28:29]
	global_store_dword v[104:105], v102, off sc1
.LBB0_382:
	v_add_u32_e32 v104, v87, v100
	v_mul_f32_e32 v102, v52, v101
	v_ashrrev_i32_e32 v105, 31, v104
	v_cvt_pk_bf16_f32 v103, v102, s0
	v_lshl_add_u64 v[104:105], v[104:105], 1, s[26:27]
	s_and_b64 vcc, exec, s[4:5]
	global_store_short v[104:105], v103, off sc1
	s_cbranch_vccnz .LBB0_384
	v_lshl_add_u32 v104, v80, 8, v100
	v_ashrrev_i32_e32 v105, 31, v104
	v_lshl_add_u64 v[104:105], v[104:105], 2, s[28:29]
	global_store_dword v[104:105], v102, off sc1
.LBB0_384:
	v_add_u32_e32 v104, v89, v100
	v_mul_f32_e32 v102, v50, v101
	v_ashrrev_i32_e32 v105, 31, v104
	v_cvt_pk_bf16_f32 v103, v102, s0
	v_lshl_add_u64 v[104:105], v[104:105], 1, s[26:27]
	s_and_b64 vcc, exec, s[4:5]
	global_store_short v[104:105], v103, off sc1
	s_cbranch_vccnz .LBB0_386
	v_lshl_add_u32 v104, v84, 8, v100
	v_ashrrev_i32_e32 v105, 31, v104
	v_lshl_add_u64 v[104:105], v[104:105], 2, s[28:29]
	global_store_dword v[104:105], v102, off sc1
.LBB0_386:
	v_add_u32_e32 v104, v91, v100
	v_mul_f32_e32 v102, v48, v101
	v_ashrrev_i32_e32 v105, 31, v104
	v_cvt_pk_bf16_f32 v103, v102, s0
	v_lshl_add_u64 v[104:105], v[104:105], 1, s[26:27]
	s_and_b64 vcc, exec, s[4:5]
	global_store_short v[104:105], v103, off sc1
	s_cbranch_vccnz .LBB0_388
	v_lshl_add_u32 v104, v86, 8, v100
	v_ashrrev_i32_e32 v105, 31, v104
	v_lshl_add_u64 v[104:105], v[104:105], 2, s[28:29]
	global_store_dword v[104:105], v102, off sc1
.LBB0_388:
	v_add_u32_e32 v104, v93, v100
	v_mul_f32_e32 v102, v40, v101
	v_ashrrev_i32_e32 v105, 31, v104
	v_cvt_pk_bf16_f32 v103, v102, s0
	v_lshl_add_u64 v[104:105], v[104:105], 1, s[26:27]
	s_and_b64 vcc, exec, s[4:5]
	global_store_short v[104:105], v103, off sc1
	s_cbranch_vccnz .LBB0_390
	v_lshl_add_u32 v104, v88, 8, v100
	v_ashrrev_i32_e32 v105, 31, v104
	v_lshl_add_u64 v[104:105], v[104:105], 2, s[28:29]
	global_store_dword v[104:105], v102, off sc1
.LBB0_390:
	v_add_u32_e32 v104, v95, v100
	v_mul_f32_e32 v102, v38, v101
	v_ashrrev_i32_e32 v105, 31, v104
	v_cvt_pk_bf16_f32 v103, v102, s0
	v_lshl_add_u64 v[104:105], v[104:105], 1, s[26:27]
	s_and_b64 vcc, exec, s[4:5]
	global_store_short v[104:105], v103, off sc1
	s_cbranch_vccnz .LBB0_392
	v_lshl_add_u32 v104, v90, 8, v100
	v_ashrrev_i32_e32 v105, 31, v104
	v_lshl_add_u64 v[104:105], v[104:105], 2, s[28:29]
	global_store_dword v[104:105], v102, off sc1
.LBB0_392:
	v_add_u32_e32 v104, v97, v100
	v_mul_f32_e32 v102, v36, v101
	v_ashrrev_i32_e32 v105, 31, v104
	v_cvt_pk_bf16_f32 v103, v102, s0
	v_lshl_add_u64 v[104:105], v[104:105], 1, s[26:27]
	s_and_b64 vcc, exec, s[4:5]
	global_store_short v[104:105], v103, off sc1
	s_cbranch_vccnz .LBB0_394
	v_lshl_add_u32 v104, v92, 8, v100
	v_ashrrev_i32_e32 v105, 31, v104
	v_lshl_add_u64 v[104:105], v[104:105], 2, s[28:29]
	global_store_dword v[104:105], v102, off sc1
.LBB0_394:
	v_add_u32_e32 v104, v98, v100
	v_mul_f32_e32 v102, v34, v101
	v_ashrrev_i32_e32 v105, 31, v104
	v_cvt_pk_bf16_f32 v103, v102, s0
	v_lshl_add_u64 v[104:105], v[104:105], 1, s[26:27]
	s_and_b64 vcc, exec, s[4:5]
	global_store_short v[104:105], v103, off sc1
	s_cbranch_vccnz .LBB0_396
	v_lshl_add_u32 v104, v94, 8, v100
	v_ashrrev_i32_e32 v105, 31, v104
	v_lshl_add_u64 v[104:105], v[104:105], 2, s[28:29]
	global_store_dword v[104:105], v102, off sc1
.LBB0_396:
	v_add_u32_e32 v102, v99, v100
	v_mul_f32_e32 v101, v32, v101
	v_ashrrev_i32_e32 v103, 31, v102
	v_cvt_pk_bf16_f32 v104, v101, s0
	v_lshl_add_u64 v[102:103], v[102:103], 1, s[26:27]
	s_and_b64 vcc, exec, s[4:5]
	global_store_short v[102:103], v104, off sc1
	s_cbranch_vccnz .LBB0_398
	v_lshl_add_u32 v102, v96, 8, v100
	v_ashrrev_i32_e32 v103, 31, v102
	v_lshl_add_u64 v[102:103], v[102:103], 2, s[28:29]
	global_store_dword v[102:103], v101, off sc1
.LBB0_398:
	global_load_dword v101, v[0:1], off offset:-1280
	v_or_b32_e32 v100, 64, v3
	v_add_u32_e32 v102, v10, v100
	v_ashrrev_i32_e32 v103, 31, v102
	v_lshl_add_u64 v[104:105], v[102:103], 1, s[26:27]
	s_and_b64 vcc, exec, s[4:5]
	s_waitcnt vmcnt(0)
	v_mul_f32_e32 v102, v57, v101
	v_cvt_pk_bf16_f32 v103, v102, s0
	global_store_short v[104:105], v103, off sc1
	s_cbranch_vccnz .LBB0_400
	v_lshl_add_u32 v104, v164, 8, v100
	v_ashrrev_i32_e32 v105, 31, v104
	v_lshl_add_u64 v[104:105], v[104:105], 2, s[28:29]
	global_store_dword v[104:105], v102, off sc1
.LBB0_400:
	v_add_u32_e32 v104, v13, v100
	v_mul_f32_e32 v102, v47, v101
	v_ashrrev_i32_e32 v105, 31, v104
	v_cvt_pk_bf16_f32 v103, v102, s0
	v_lshl_add_u64 v[104:105], v[104:105], 1, s[26:27]
	s_and_b64 vcc, exec, s[4:5]
	global_store_short v[104:105], v103, off sc1
	s_cbranch_vccnz .LBB0_402
	v_lshl_add_u32 v104, v2, 8, v100
	v_ashrrev_i32_e32 v105, 31, v104
	v_lshl_add_u64 v[104:105], v[104:105], 2, s[28:29]
	global_store_dword v[104:105], v102, off sc1
.LBB0_402:
	v_add_u32_e32 v104, v15, v100
	v_mul_f32_e32 v102, v46, v101
	v_ashrrev_i32_e32 v105, 31, v104
	v_cvt_pk_bf16_f32 v103, v102, s0
	v_lshl_add_u64 v[104:105], v[104:105], 1, s[26:27]
	s_and_b64 vcc, exec, s[4:5]
	global_store_short v[104:105], v103, off sc1
	s_cbranch_vccnz .LBB0_404
	v_lshl_add_u32 v104, v11, 8, v100
	v_ashrrev_i32_e32 v105, 31, v104
	v_lshl_add_u64 v[104:105], v[104:105], 2, s[28:29]
	global_store_dword v[104:105], v102, off sc1
.LBB0_404:
	v_add_u32_e32 v104, v59, v100
	v_mul_f32_e32 v102, v45, v101
	v_ashrrev_i32_e32 v105, 31, v104
	v_cvt_pk_bf16_f32 v103, v102, s0
	v_lshl_add_u64 v[104:105], v[104:105], 1, s[26:27]
	s_and_b64 vcc, exec, s[4:5]
	global_store_short v[104:105], v103, off sc1
	s_cbranch_vccnz .LBB0_406
	v_lshl_add_u32 v104, v12, 8, v100
	v_ashrrev_i32_e32 v105, 31, v104
	v_lshl_add_u64 v[104:105], v[104:105], 2, s[28:29]
	global_store_dword v[104:105], v102, off sc1
.LBB0_406:
	v_add_u32_e32 v104, v61, v100
	v_mul_f32_e32 v102, v44, v101
	v_ashrrev_i32_e32 v105, 31, v104
	v_cvt_pk_bf16_f32 v103, v102, s0
	v_lshl_add_u64 v[104:105], v[104:105], 1, s[26:27]
	s_and_b64 vcc, exec, s[4:5]
	global_store_short v[104:105], v103, off sc1
	s_cbranch_vccnz .LBB0_408
	v_lshl_add_u32 v104, v14, 8, v100
	v_ashrrev_i32_e32 v105, 31, v104
	v_lshl_add_u64 v[104:105], v[104:105], 2, s[28:29]
	global_store_dword v[104:105], v102, off sc1
.LBB0_408:
	v_add_u32_e32 v104, v63, v100
	v_mul_f32_e32 v102, v43, v101
	v_ashrrev_i32_e32 v105, 31, v104
	v_cvt_pk_bf16_f32 v103, v102, s0
	v_lshl_add_u64 v[104:105], v[104:105], 1, s[26:27]
	s_and_b64 vcc, exec, s[4:5]
	global_store_short v[104:105], v103, off sc1
	s_cbranch_vccnz .LBB0_410
	v_lshl_add_u32 v104, v58, 8, v100
	v_ashrrev_i32_e32 v105, 31, v104
	v_lshl_add_u64 v[104:105], v[104:105], 2, s[28:29]
	global_store_dword v[104:105], v102, off sc1
.LBB0_410:
	v_add_u32_e32 v104, v81, v100
	v_mul_f32_e32 v102, v42, v101
	v_ashrrev_i32_e32 v105, 31, v104
	v_cvt_pk_bf16_f32 v103, v102, s0
	v_lshl_add_u64 v[104:105], v[104:105], 1, s[26:27]
	s_and_b64 vcc, exec, s[4:5]
	global_store_short v[104:105], v103, off sc1
	s_cbranch_vccnz .LBB0_412
	v_lshl_add_u32 v104, v60, 8, v100
	v_ashrrev_i32_e32 v105, 31, v104
	v_lshl_add_u64 v[104:105], v[104:105], 2, s[28:29]
	global_store_dword v[104:105], v102, off sc1
.LBB0_412:
	v_add_u32_e32 v104, v85, v100
	v_mul_f32_e32 v102, v23, v101
	v_ashrrev_i32_e32 v105, 31, v104
	v_cvt_pk_bf16_f32 v103, v102, s0
	v_lshl_add_u64 v[104:105], v[104:105], 1, s[26:27]
	s_and_b64 vcc, exec, s[4:5]
	global_store_short v[104:105], v103, off sc1
	s_cbranch_vccnz .LBB0_414
	v_lshl_add_u32 v104, v62, 8, v100
	v_ashrrev_i32_e32 v105, 31, v104
	v_lshl_add_u64 v[104:105], v[104:105], 2, s[28:29]
	global_store_dword v[104:105], v102, off sc1
.LBB0_414:
	v_add_u32_e32 v104, v87, v100
	v_mul_f32_e32 v102, v22, v101
	v_ashrrev_i32_e32 v105, 31, v104
	v_cvt_pk_bf16_f32 v103, v102, s0
	v_lshl_add_u64 v[104:105], v[104:105], 1, s[26:27]
	s_and_b64 vcc, exec, s[4:5]
	global_store_short v[104:105], v103, off sc1
	s_cbranch_vccnz .LBB0_416
	v_lshl_add_u32 v104, v80, 8, v100
	v_ashrrev_i32_e32 v105, 31, v104
	v_lshl_add_u64 v[104:105], v[104:105], 2, s[28:29]
	global_store_dword v[104:105], v102, off sc1
.LBB0_416:
	v_add_u32_e32 v104, v89, v100
	v_mul_f32_e32 v102, v21, v101
	v_ashrrev_i32_e32 v105, 31, v104
	v_cvt_pk_bf16_f32 v103, v102, s0
	v_lshl_add_u64 v[104:105], v[104:105], 1, s[26:27]
	s_and_b64 vcc, exec, s[4:5]
	global_store_short v[104:105], v103, off sc1
	s_cbranch_vccnz .LBB0_418
	v_lshl_add_u32 v104, v84, 8, v100
	v_ashrrev_i32_e32 v105, 31, v104
	v_lshl_add_u64 v[104:105], v[104:105], 2, s[28:29]
	global_store_dword v[104:105], v102, off sc1
.LBB0_418:
	v_add_u32_e32 v104, v91, v100
	v_mul_f32_e32 v102, v20, v101
	v_ashrrev_i32_e32 v105, 31, v104
	v_cvt_pk_bf16_f32 v103, v102, s0
	v_lshl_add_u64 v[104:105], v[104:105], 1, s[26:27]
	s_and_b64 vcc, exec, s[4:5]
	global_store_short v[104:105], v103, off sc1
	s_cbranch_vccnz .LBB0_420
	v_lshl_add_u32 v104, v86, 8, v100
	v_ashrrev_i32_e32 v105, 31, v104
	v_lshl_add_u64 v[104:105], v[104:105], 2, s[28:29]
	global_store_dword v[104:105], v102, off sc1
.LBB0_420:
	v_add_u32_e32 v104, v93, v100
	v_mul_f32_e32 v102, v19, v101
	v_ashrrev_i32_e32 v105, 31, v104
	v_cvt_pk_bf16_f32 v103, v102, s0
	v_lshl_add_u64 v[104:105], v[104:105], 1, s[26:27]
	s_and_b64 vcc, exec, s[4:5]
	global_store_short v[104:105], v103, off sc1
	s_cbranch_vccnz .LBB0_422
	v_lshl_add_u32 v104, v88, 8, v100
	v_ashrrev_i32_e32 v105, 31, v104
	v_lshl_add_u64 v[104:105], v[104:105], 2, s[28:29]
	global_store_dword v[104:105], v102, off sc1
.LBB0_422:
	v_add_u32_e32 v104, v95, v100
	v_mul_f32_e32 v102, v18, v101
	v_ashrrev_i32_e32 v105, 31, v104
	v_cvt_pk_bf16_f32 v103, v102, s0
	v_lshl_add_u64 v[104:105], v[104:105], 1, s[26:27]
	s_and_b64 vcc, exec, s[4:5]
	global_store_short v[104:105], v103, off sc1
	s_cbranch_vccnz .LBB0_424
	v_lshl_add_u32 v104, v90, 8, v100
	v_ashrrev_i32_e32 v105, 31, v104
	v_lshl_add_u64 v[104:105], v[104:105], 2, s[28:29]
	global_store_dword v[104:105], v102, off sc1
.LBB0_424:
	v_add_u32_e32 v104, v97, v100
	v_mul_f32_e32 v102, v17, v101
	v_ashrrev_i32_e32 v105, 31, v104
	v_cvt_pk_bf16_f32 v103, v102, s0
	v_lshl_add_u64 v[104:105], v[104:105], 1, s[26:27]
	s_and_b64 vcc, exec, s[4:5]
	global_store_short v[104:105], v103, off sc1
	s_cbranch_vccnz .LBB0_426
	v_lshl_add_u32 v104, v92, 8, v100
	v_ashrrev_i32_e32 v105, 31, v104
	v_lshl_add_u64 v[104:105], v[104:105], 2, s[28:29]
	global_store_dword v[104:105], v102, off sc1
.LBB0_426:
	v_add_u32_e32 v104, v98, v100
	v_mul_f32_e32 v102, v16, v101
	v_ashrrev_i32_e32 v105, 31, v104
	v_cvt_pk_bf16_f32 v103, v102, s0
	v_lshl_add_u64 v[104:105], v[104:105], 1, s[26:27]
	s_and_b64 vcc, exec, s[4:5]
	global_store_short v[104:105], v103, off sc1
	s_cbranch_vccnz .LBB0_428
	v_lshl_add_u32 v104, v94, 8, v100
	v_ashrrev_i32_e32 v105, 31, v104
	v_lshl_add_u64 v[104:105], v[104:105], 2, s[28:29]
	global_store_dword v[104:105], v102, off sc1
.LBB0_428:
	v_add_u32_e32 v102, v99, v100
	v_mul_f32_e32 v101, v82, v101
	v_ashrrev_i32_e32 v103, 31, v102
	v_cvt_pk_bf16_f32 v104, v101, s0
	v_lshl_add_u64 v[102:103], v[102:103], 1, s[26:27]
	s_and_b64 vcc, exec, s[4:5]
	global_store_short v[102:103], v104, off sc1
	s_cbranch_vccnz .LBB0_430
	v_lshl_add_u32 v102, v96, 8, v100
	v_ashrrev_i32_e32 v103, 31, v102
	v_lshl_add_u64 v[102:103], v[102:103], 2, s[28:29]
	global_store_dword v[102:103], v101, off sc1
.LBB0_430:
	global_load_dword v1, v[0:1], off offset:-1152
	v_or_b32_e32 v0, 0x60, v3
	v_add_u32_e32 v100, v10, v0
	v_ashrrev_i32_e32 v101, 31, v100
	v_lshl_add_u64 v[100:101], v[100:101], 1, s[26:27]
	s_and_b64 vcc, exec, s[4:5]
	s_waitcnt vmcnt(0)
	v_mul_f32_e32 v3, v56, v1
	v_cvt_pk_bf16_f32 v10, v3, s0
	global_store_short v[100:101], v10, off sc1
	s_cbranch_vccnz .LBB0_432
	v_lshl_add_u32 v100, v164, 8, v0
	v_ashrrev_i32_e32 v101, 31, v100
	v_lshl_add_u64 v[100:101], v[100:101], 2, s[28:29]
	global_store_dword v[100:101], v3, off sc1
.LBB0_432:
	v_add_u32_e32 v100, v13, v0
	v_mul_f32_e32 v3, v31, v1
	v_ashrrev_i32_e32 v101, 31, v100
	v_cvt_pk_bf16_f32 v10, v3, s0
	v_lshl_add_u64 v[100:101], v[100:101], 1, s[26:27]
	s_and_b64 vcc, exec, s[4:5]
	global_store_short v[100:101], v10, off sc1
	s_cbranch_vccnz .LBB0_434
	v_lshl_add_u32 v100, v2, 8, v0
	v_ashrrev_i32_e32 v101, 31, v100
	v_lshl_add_u64 v[100:101], v[100:101], 2, s[28:29]
	global_store_dword v[100:101], v3, off sc1
.LBB0_434:
	v_add_u32_e32 v100, v15, v0
	v_mul_f32_e32 v2, v30, v1
	v_ashrrev_i32_e32 v101, 31, v100
	v_cvt_pk_bf16_f32 v3, v2, s0
	v_lshl_add_u64 v[100:101], v[100:101], 1, s[26:27]
	s_and_b64 vcc, exec, s[4:5]
	global_store_short v[100:101], v3, off sc1
	s_cbranch_vccnz .LBB0_436
	v_lshl_add_u32 v10, v11, 8, v0
	v_ashrrev_i32_e32 v11, 31, v10
	v_lshl_add_u64 v[10:11], v[10:11], 2, s[28:29]
	global_store_dword v[10:11], v2, off sc1
.LBB0_436:
	v_add_u32_e32 v10, v59, v0
	v_mul_f32_e32 v2, v29, v1
	v_ashrrev_i32_e32 v11, 31, v10
	v_cvt_pk_bf16_f32 v3, v2, s0
	v_lshl_add_u64 v[10:11], v[10:11], 1, s[26:27]
	s_and_b64 vcc, exec, s[4:5]
	global_store_short v[10:11], v3, off sc1
	s_cbranch_vccnz .LBB0_438
	v_lshl_add_u32 v10, v12, 8, v0
	v_ashrrev_i32_e32 v11, 31, v10
	v_lshl_add_u64 v[10:11], v[10:11], 2, s[28:29]
	global_store_dword v[10:11], v2, off sc1
.LBB0_438:
	v_add_u32_e32 v10, v61, v0
	v_mul_f32_e32 v2, v28, v1
	v_ashrrev_i32_e32 v11, 31, v10
	v_cvt_pk_bf16_f32 v3, v2, s0
	v_lshl_add_u64 v[10:11], v[10:11], 1, s[26:27]
	s_and_b64 vcc, exec, s[4:5]
	global_store_short v[10:11], v3, off sc1
	s_cbranch_vccnz .LBB0_440
	v_lshl_add_u32 v10, v14, 8, v0
	v_ashrrev_i32_e32 v11, 31, v10
	v_lshl_add_u64 v[10:11], v[10:11], 2, s[28:29]
	global_store_dword v[10:11], v2, off sc1
.LBB0_440:
	v_add_u32_e32 v10, v63, v0
	v_mul_f32_e32 v2, v27, v1
	v_ashrrev_i32_e32 v11, 31, v10
	v_cvt_pk_bf16_f32 v3, v2, s0
	v_lshl_add_u64 v[10:11], v[10:11], 1, s[26:27]
	s_and_b64 vcc, exec, s[4:5]
	global_store_short v[10:11], v3, off sc1
	s_cbranch_vccnz .LBB0_442
	v_lshl_add_u32 v10, v58, 8, v0
	v_ashrrev_i32_e32 v11, 31, v10
	v_lshl_add_u64 v[10:11], v[10:11], 2, s[28:29]
	global_store_dword v[10:11], v2, off sc1
.LBB0_442:
	v_add_u32_e32 v10, v81, v0
	v_mul_f32_e32 v2, v26, v1
	v_ashrrev_i32_e32 v11, 31, v10
	v_cvt_pk_bf16_f32 v3, v2, s0
	v_lshl_add_u64 v[10:11], v[10:11], 1, s[26:27]
	s_and_b64 vcc, exec, s[4:5]
	global_store_short v[10:11], v3, off sc1
	s_cbranch_vccnz .LBB0_444
	v_lshl_add_u32 v10, v60, 8, v0
	v_ashrrev_i32_e32 v11, 31, v10
	v_lshl_add_u64 v[10:11], v[10:11], 2, s[28:29]
	global_store_dword v[10:11], v2, off sc1
.LBB0_444:
	v_add_u32_e32 v10, v85, v0
	v_mul_f32_e32 v2, v25, v1
	v_ashrrev_i32_e32 v11, 31, v10
	v_cvt_pk_bf16_f32 v3, v2, s0
	v_lshl_add_u64 v[10:11], v[10:11], 1, s[26:27]
	s_and_b64 vcc, exec, s[4:5]
	global_store_short v[10:11], v3, off sc1
	s_cbranch_vccnz .LBB0_446
	v_lshl_add_u32 v10, v62, 8, v0
	v_ashrrev_i32_e32 v11, 31, v10
	v_lshl_add_u64 v[10:11], v[10:11], 2, s[28:29]
	global_store_dword v[10:11], v2, off sc1
.LBB0_446:
	v_add_u32_e32 v10, v87, v0
	v_mul_f32_e32 v2, v24, v1
	v_ashrrev_i32_e32 v11, 31, v10
	v_cvt_pk_bf16_f32 v3, v2, s0
	v_lshl_add_u64 v[10:11], v[10:11], 1, s[26:27]
	s_and_b64 vcc, exec, s[4:5]
	global_store_short v[10:11], v3, off sc1
	s_cbranch_vccnz .LBB0_448
	v_lshl_add_u32 v10, v80, 8, v0
	v_ashrrev_i32_e32 v11, 31, v10
	v_lshl_add_u64 v[10:11], v[10:11], 2, s[28:29]
	global_store_dword v[10:11], v2, off sc1
.LBB0_448:
	v_add_u32_e32 v10, v89, v0
	v_mul_f32_e32 v2, v9, v1
	v_ashrrev_i32_e32 v11, 31, v10
	v_cvt_pk_bf16_f32 v3, v2, s0
	v_lshl_add_u64 v[10:11], v[10:11], 1, s[26:27]
	s_and_b64 vcc, exec, s[4:5]
	global_store_short v[10:11], v3, off sc1
	s_cbranch_vccnz .LBB0_450
	v_lshl_add_u32 v10, v84, 8, v0
	v_ashrrev_i32_e32 v11, 31, v10
	v_lshl_add_u64 v[10:11], v[10:11], 2, s[28:29]
	global_store_dword v[10:11], v2, off sc1
.LBB0_450:
	v_add_u32_e32 v10, v91, v0
	v_mul_f32_e32 v2, v8, v1
	v_ashrrev_i32_e32 v11, 31, v10
	v_cvt_pk_bf16_f32 v3, v2, s0
	v_lshl_add_u64 v[10:11], v[10:11], 1, s[26:27]
	s_and_b64 vcc, exec, s[4:5]
	global_store_short v[10:11], v3, off sc1
	s_cbranch_vccnz .LBB0_452
	v_lshl_add_u32 v10, v86, 8, v0
	v_ashrrev_i32_e32 v11, 31, v10
	v_lshl_add_u64 v[10:11], v[10:11], 2, s[28:29]
	global_store_dword v[10:11], v2, off sc1
.LBB0_452:
	v_add_u32_e32 v10, v93, v0
	v_mul_f32_e32 v2, v7, v1
	v_ashrrev_i32_e32 v11, 31, v10
	v_cvt_pk_bf16_f32 v3, v2, s0
	v_lshl_add_u64 v[10:11], v[10:11], 1, s[26:27]
	s_and_b64 vcc, exec, s[4:5]
	global_store_short v[10:11], v3, off sc1
	s_cbranch_vccnz .LBB0_454
	v_lshl_add_u32 v10, v88, 8, v0
	v_ashrrev_i32_e32 v11, 31, v10
	v_lshl_add_u64 v[10:11], v[10:11], 2, s[28:29]
	global_store_dword v[10:11], v2, off sc1
.LBB0_454:
	v_add_u32_e32 v10, v95, v0
	v_mul_f32_e32 v2, v6, v1
	v_ashrrev_i32_e32 v11, 31, v10
	v_cvt_pk_bf16_f32 v3, v2, s0
	v_lshl_add_u64 v[10:11], v[10:11], 1, s[26:27]
	s_and_b64 vcc, exec, s[4:5]
	global_store_short v[10:11], v3, off sc1
	s_cbranch_vccnz .LBB0_456
	v_lshl_add_u32 v10, v90, 8, v0
	v_ashrrev_i32_e32 v11, 31, v10
	v_lshl_add_u64 v[10:11], v[10:11], 2, s[28:29]
	global_store_dword v[10:11], v2, off sc1
.LBB0_456:
	v_add_u32_e32 v10, v97, v0
	v_mul_f32_e32 v2, v5, v1
	v_ashrrev_i32_e32 v11, 31, v10
	v_cvt_pk_bf16_f32 v3, v2, s0
	v_lshl_add_u64 v[10:11], v[10:11], 1, s[26:27]
	s_and_b64 vcc, exec, s[4:5]
	global_store_short v[10:11], v3, off sc1
	s_cbranch_vccnz .LBB0_458
	v_lshl_add_u32 v10, v92, 8, v0
	v_ashrrev_i32_e32 v11, 31, v10
	v_lshl_add_u64 v[10:11], v[10:11], 2, s[28:29]
	global_store_dword v[10:11], v2, off sc1
.LBB0_458:
	v_add_u32_e32 v10, v98, v0
	v_mul_f32_e32 v2, v4, v1
	v_ashrrev_i32_e32 v11, 31, v10
	v_cvt_pk_bf16_f32 v3, v2, s0
	v_lshl_add_u64 v[10:11], v[10:11], 1, s[26:27]
	s_and_b64 vcc, exec, s[4:5]
	global_store_short v[10:11], v3, off sc1
	s_cbranch_vccnz .LBB0_460
	v_lshl_add_u32 v10, v94, 8, v0
	v_ashrrev_i32_e32 v11, 31, v10
	v_lshl_add_u64 v[10:11], v[10:11], 2, s[28:29]
	global_store_dword v[10:11], v2, off sc1
.LBB0_460:
	v_add_u32_e32 v2, v99, v0
	v_mul_f32_e32 v1, v83, v1
	v_ashrrev_i32_e32 v3, 31, v2
	v_cvt_pk_bf16_f32 v10, v1, s0
	v_lshl_add_u64 v[2:3], v[2:3], 1, s[26:27]
	s_and_b64 vcc, exec, s[4:5]
	global_store_short v[2:3], v10, off sc1
	s_cbranch_vccnz .LBB0_462
	v_lshl_add_u32 v2, v96, 8, v0
	v_ashrrev_i32_e32 v3, 31, v2
	v_lshl_add_u64 v[2:3], v[2:3], 2, s[28:29]
	global_store_dword v[2:3], v1, off sc1
.LBB0_462:
	v_pk_mul_f32 v[0:1], v[78:79], v[78:79]
	v_and_b32_e32 v2, 64, v214
	v_add_f32_e32 v0, v1, v0
	v_xor_b32_e32 v1, 1, v214
	v_add_u32_e32 v12, 64, v2
	v_cmp_lt_i32_e32 vcc, v1, v12
	v_fmac_f32_e32 v0, v57, v57
	v_fmac_f32_e32 v0, v56, v56
	v_cndmask_b32_e32 v1, v214, v1, vcc
	v_lshlrev_b32_e32 v2, 2, v1
	ds_bpermute_b32 v1, v2, v0
	v_xor_b32_e32 v3, 2, v214
	v_cmp_lt_i32_e32 vcc, v3, v12
	v_xor_b32_e32 v10, 4, v214
	v_xor_b32_e32 v11, 8, v214
	v_cndmask_b32_e32 v3, v214, v3, vcc
	v_lshlrev_b32_e32 v3, 2, v3
	s_waitcnt lgkmcnt(0)
	v_add_f32_e32 v0, v0, v1
	ds_bpermute_b32 v1, v3, v0
	v_cmp_lt_i32_e32 vcc, v10, v12
	v_xor_b32_e32 v13, 16, v214
	s_mul_i32 s4, s10, 0x4200
	v_cndmask_b32_e32 v10, v214, v10, vcc
	v_lshlrev_b32_e32 v10, 2, v10
	s_waitcnt lgkmcnt(0)
	v_add_f32_e32 v0, v0, v1
	ds_bpermute_b32 v1, v10, v0
	v_cmp_lt_i32_e32 vcc, v11, v12
	s_add_i32 s11, s11, s4
	s_waitcnt lgkmcnt(0)
	v_add_f32_e32 v0, v0, v1
	v_cndmask_b32_e32 v11, v214, v11, vcc
	v_lshlrev_b32_e32 v11, 2, v11
	ds_bpermute_b32 v1, v11, v0
	v_cmp_lt_i32_e32 vcc, v13, v12
	s_waitcnt lgkmcnt(0)
	v_add_f32_e32 v1, v0, v1
	v_cndmask_b32_e32 v12, v214, v13, vcc
	v_lshlrev_b32_e32 v12, 2, v12
	ds_bpermute_b32 v13, v12, v1
	v_add_u32_e32 v0, s11, v191
	s_and_saveexec_b64 s[4:5], s[0:1]
	s_cbranch_execz .LBB0_464
	s_waitcnt lgkmcnt(0)
	v_add_f32_e32 v13, v1, v13
	v_ashrrev_i32_e32 v1, 31, v0
	v_lshl_add_u64 v[14:15], v[0:1], 2, s[30:31]
	global_store_dword v[14:15], v13, off sc1
.LBB0_464:
	s_or_b64 exec, exec, s[4:5]
	v_pk_mul_f32 v[14:15], v[74:75], v[74:75]
	s_nop 0
	v_add_f32_e32 v1, v15, v14
	v_fmac_f32_e32 v1, v47, v47
	v_fmac_f32_e32 v1, v31, v31
	s_waitcnt lgkmcnt(0)
	ds_bpermute_b32 v13, v2, v1
	s_waitcnt lgkmcnt(0)
	v_add_f32_e32 v1, v1, v13
	ds_bpermute_b32 v13, v3, v1
	s_waitcnt lgkmcnt(0)
	v_add_f32_e32 v1, v1, v13
	ds_bpermute_b32 v13, v10, v1
	s_waitcnt lgkmcnt(0)
	v_add_f32_e32 v1, v1, v13
	ds_bpermute_b32 v13, v11, v1
	s_waitcnt lgkmcnt(0)
	v_add_f32_e32 v1, v1, v13
	ds_bpermute_b32 v13, v12, v1
	s_and_saveexec_b64 s[4:5], s[0:1]
	s_cbranch_execz .LBB0_466
	v_add_u32_e32 v14, 1, v0
	v_ashrrev_i32_e32 v15, 31, v14
	s_waitcnt lgkmcnt(0)
	v_add_f32_e32 v1, v1, v13
	v_lshl_add_u64 v[14:15], v[14:15], 2, s[30:31]
	global_store_dword v[14:15], v1, off sc1
.LBB0_466:
	s_or_b64 exec, exec, s[4:5]
	v_pk_mul_f32 v[14:15], v[72:73], v[72:73]
	s_nop 0
	v_add_f32_e32 v1, v15, v14
	v_fmac_f32_e32 v1, v46, v46
	v_fmac_f32_e32 v1, v30, v30
	s_waitcnt lgkmcnt(0)
	ds_bpermute_b32 v13, v2, v1
	s_waitcnt lgkmcnt(0)
	v_add_f32_e32 v1, v1, v13
	ds_bpermute_b32 v13, v3, v1
	s_waitcnt lgkmcnt(0)
	v_add_f32_e32 v1, v1, v13
	ds_bpermute_b32 v13, v10, v1
	s_waitcnt lgkmcnt(0)
	v_add_f32_e32 v1, v1, v13
	ds_bpermute_b32 v13, v11, v1
	s_waitcnt lgkmcnt(0)
	v_add_f32_e32 v1, v1, v13
	ds_bpermute_b32 v13, v12, v1
	s_and_saveexec_b64 s[4:5], s[0:1]
	s_cbranch_execz .LBB0_468
	v_add_u32_e32 v14, 2, v0
	v_ashrrev_i32_e32 v15, 31, v14
	s_waitcnt lgkmcnt(0)
	v_add_f32_e32 v1, v1, v13
	v_lshl_add_u64 v[14:15], v[14:15], 2, s[30:31]
	global_store_dword v[14:15], v1, off sc1
.LBB0_468:
	s_or_b64 exec, exec, s[4:5]
	v_pk_mul_f32 v[14:15], v[70:71], v[70:71]
	s_nop 0
	v_add_f32_e32 v1, v15, v14
	v_fmac_f32_e32 v1, v45, v45
	v_fmac_f32_e32 v1, v29, v29
	s_waitcnt lgkmcnt(0)
	ds_bpermute_b32 v13, v2, v1
	s_waitcnt lgkmcnt(0)
	v_add_f32_e32 v1, v1, v13
	ds_bpermute_b32 v13, v3, v1
	s_waitcnt lgkmcnt(0)
	v_add_f32_e32 v1, v1, v13
	ds_bpermute_b32 v13, v10, v1
	s_waitcnt lgkmcnt(0)
	v_add_f32_e32 v1, v1, v13
	ds_bpermute_b32 v13, v11, v1
	s_waitcnt lgkmcnt(0)
	v_add_f32_e32 v1, v1, v13
	ds_bpermute_b32 v13, v12, v1
	s_and_saveexec_b64 s[4:5], s[0:1]
	s_cbranch_execz .LBB0_470
	v_add_u32_e32 v14, 3, v0
	v_ashrrev_i32_e32 v15, 31, v14
	s_waitcnt lgkmcnt(0)
	v_add_f32_e32 v1, v1, v13
	v_lshl_add_u64 v[14:15], v[14:15], 2, s[30:31]
	global_store_dword v[14:15], v1, off sc1
.LBB0_470:
	s_or_b64 exec, exec, s[4:5]
	v_pk_mul_f32 v[14:15], v[68:69], v[68:69]
	s_nop 0
	v_add_f32_e32 v1, v15, v14
	v_fmac_f32_e32 v1, v44, v44
	v_fmac_f32_e32 v1, v28, v28
	s_waitcnt lgkmcnt(0)
	ds_bpermute_b32 v13, v2, v1
	s_waitcnt lgkmcnt(0)
	v_add_f32_e32 v1, v1, v13
	ds_bpermute_b32 v13, v3, v1
	s_waitcnt lgkmcnt(0)
	v_add_f32_e32 v1, v1, v13
	ds_bpermute_b32 v13, v10, v1
	s_waitcnt lgkmcnt(0)
	v_add_f32_e32 v1, v1, v13
	ds_bpermute_b32 v13, v11, v1
	s_waitcnt lgkmcnt(0)
	v_add_f32_e32 v1, v1, v13
	ds_bpermute_b32 v13, v12, v1
	s_and_saveexec_b64 s[4:5], s[0:1]
	s_cbranch_execz .LBB0_472
	v_add_u32_e32 v14, 8, v0
	v_ashrrev_i32_e32 v15, 31, v14
	s_waitcnt lgkmcnt(0)
	v_add_f32_e32 v1, v1, v13
	v_lshl_add_u64 v[14:15], v[14:15], 2, s[30:31]
	global_store_dword v[14:15], v1, off sc1
.LBB0_472:
	s_or_b64 exec, exec, s[4:5]
	v_pk_mul_f32 v[14:15], v[66:67], v[66:67]
	s_nop 0
	v_add_f32_e32 v1, v15, v14
	v_fmac_f32_e32 v1, v43, v43
	v_fmac_f32_e32 v1, v27, v27
	s_waitcnt lgkmcnt(0)
	ds_bpermute_b32 v13, v2, v1
	s_waitcnt lgkmcnt(0)
	v_add_f32_e32 v1, v1, v13
	ds_bpermute_b32 v13, v3, v1
	s_waitcnt lgkmcnt(0)
	v_add_f32_e32 v1, v1, v13
	ds_bpermute_b32 v13, v10, v1
	s_waitcnt lgkmcnt(0)
	v_add_f32_e32 v1, v1, v13
	ds_bpermute_b32 v13, v11, v1
	s_waitcnt lgkmcnt(0)
	v_add_f32_e32 v1, v1, v13
	ds_bpermute_b32 v13, v12, v1
	s_and_saveexec_b64 s[4:5], s[0:1]
	s_cbranch_execz .LBB0_474
	v_add_u32_e32 v14, 9, v0
	v_ashrrev_i32_e32 v15, 31, v14
	s_waitcnt lgkmcnt(0)
	v_add_f32_e32 v1, v1, v13
	v_lshl_add_u64 v[14:15], v[14:15], 2, s[30:31]
	global_store_dword v[14:15], v1, off sc1
.LBB0_474:
	s_or_b64 exec, exec, s[4:5]
	v_pk_mul_f32 v[14:15], v[64:65], v[64:65]
	s_nop 0
	v_add_f32_e32 v1, v15, v14
	v_fmac_f32_e32 v1, v42, v42
	v_fmac_f32_e32 v1, v26, v26
	s_waitcnt lgkmcnt(0)
	ds_bpermute_b32 v13, v2, v1
	s_waitcnt lgkmcnt(0)
	v_add_f32_e32 v1, v1, v13
	ds_bpermute_b32 v13, v3, v1
	s_waitcnt lgkmcnt(0)
	v_add_f32_e32 v1, v1, v13
	ds_bpermute_b32 v13, v10, v1
	s_waitcnt lgkmcnt(0)
	v_add_f32_e32 v1, v1, v13
	ds_bpermute_b32 v13, v11, v1
	s_waitcnt lgkmcnt(0)
	v_add_f32_e32 v1, v1, v13
	ds_bpermute_b32 v13, v12, v1
	s_and_saveexec_b64 s[4:5], s[0:1]
	s_cbranch_execz .LBB0_476
	v_add_u32_e32 v14, 10, v0
	v_ashrrev_i32_e32 v15, 31, v14
	s_waitcnt lgkmcnt(0)
	v_add_f32_e32 v1, v1, v13
	v_lshl_add_u64 v[14:15], v[14:15], 2, s[30:31]
	global_store_dword v[14:15], v1, off sc1
.LBB0_476:
	s_or_b64 exec, exec, s[4:5]
	v_pk_mul_f32 v[14:15], v[54:55], v[54:55]
	s_nop 0
	v_add_f32_e32 v1, v15, v14
	v_fmac_f32_e32 v1, v23, v23
	v_fmac_f32_e32 v1, v25, v25
	s_waitcnt lgkmcnt(0)
	ds_bpermute_b32 v13, v2, v1
	s_waitcnt lgkmcnt(0)
	v_add_f32_e32 v1, v1, v13
	ds_bpermute_b32 v13, v3, v1
	s_waitcnt lgkmcnt(0)
	v_add_f32_e32 v1, v1, v13
	ds_bpermute_b32 v13, v10, v1
	s_waitcnt lgkmcnt(0)
	v_add_f32_e32 v1, v1, v13
	ds_bpermute_b32 v13, v11, v1
	s_waitcnt lgkmcnt(0)
	v_add_f32_e32 v1, v1, v13
	ds_bpermute_b32 v13, v12, v1
	s_and_saveexec_b64 s[4:5], s[0:1]
	s_cbranch_execz .LBB0_478
	v_add_u32_e32 v14, 11, v0
	v_ashrrev_i32_e32 v15, 31, v14
	s_waitcnt lgkmcnt(0)
	v_add_f32_e32 v1, v1, v13
	v_lshl_add_u64 v[14:15], v[14:15], 2, s[30:31]
	global_store_dword v[14:15], v1, off sc1
.LBB0_478:
	s_or_b64 exec, exec, s[4:5]
	v_pk_mul_f32 v[14:15], v[52:53], v[52:53]
	s_nop 0
	v_add_f32_e32 v1, v15, v14
	v_fmac_f32_e32 v1, v22, v22
	v_fmac_f32_e32 v1, v24, v24
	s_waitcnt lgkmcnt(0)
	ds_bpermute_b32 v13, v2, v1
	s_waitcnt lgkmcnt(0)
	v_add_f32_e32 v1, v1, v13
	ds_bpermute_b32 v13, v3, v1
	s_waitcnt lgkmcnt(0)
	v_add_f32_e32 v1, v1, v13
	ds_bpermute_b32 v13, v10, v1
	s_waitcnt lgkmcnt(0)
	v_add_f32_e32 v1, v1, v13
	ds_bpermute_b32 v13, v11, v1
	s_waitcnt lgkmcnt(0)
	v_add_f32_e32 v1, v1, v13
	ds_bpermute_b32 v13, v12, v1
	s_and_saveexec_b64 s[4:5], s[0:1]
	s_cbranch_execz .LBB0_480
	v_add_u32_e32 v14, 16, v0
	v_ashrrev_i32_e32 v15, 31, v14
	s_waitcnt lgkmcnt(0)
	v_add_f32_e32 v1, v1, v13
	v_lshl_add_u64 v[14:15], v[14:15], 2, s[30:31]
	global_store_dword v[14:15], v1, off sc1
.LBB0_480:
	s_or_b64 exec, exec, s[4:5]
	v_pk_mul_f32 v[14:15], v[50:51], v[50:51]
	s_nop 0
	v_add_f32_e32 v1, v15, v14
	v_fmac_f32_e32 v1, v21, v21
	v_fmac_f32_e32 v1, v9, v9
	s_waitcnt lgkmcnt(0)
	ds_bpermute_b32 v13, v2, v1
	s_waitcnt lgkmcnt(0)
	v_add_f32_e32 v1, v1, v13
	ds_bpermute_b32 v13, v3, v1
	s_waitcnt lgkmcnt(0)
	v_add_f32_e32 v1, v1, v13
	ds_bpermute_b32 v13, v10, v1
	s_waitcnt lgkmcnt(0)
	v_add_f32_e32 v1, v1, v13
	ds_bpermute_b32 v13, v11, v1
	s_waitcnt lgkmcnt(0)
	v_add_f32_e32 v1, v1, v13
	ds_bpermute_b32 v13, v12, v1
	s_and_saveexec_b64 s[4:5], s[0:1]
	s_cbranch_execz .LBB0_482
	v_add_u32_e32 v14, 17, v0
	v_ashrrev_i32_e32 v15, 31, v14
	s_waitcnt lgkmcnt(0)
	v_add_f32_e32 v1, v1, v13
	v_lshl_add_u64 v[14:15], v[14:15], 2, s[30:31]
	global_store_dword v[14:15], v1, off sc1
.LBB0_482:
	s_or_b64 exec, exec, s[4:5]
	v_pk_mul_f32 v[14:15], v[48:49], v[48:49]
	s_nop 0
	v_add_f32_e32 v1, v15, v14
	v_fmac_f32_e32 v1, v20, v20
	v_fmac_f32_e32 v1, v8, v8
	s_waitcnt lgkmcnt(0)
	ds_bpermute_b32 v13, v2, v1
	s_waitcnt lgkmcnt(0)
	v_add_f32_e32 v1, v1, v13
	ds_bpermute_b32 v13, v3, v1
	s_waitcnt lgkmcnt(0)
	v_add_f32_e32 v1, v1, v13
	ds_bpermute_b32 v13, v10, v1
	s_waitcnt lgkmcnt(0)
	v_add_f32_e32 v1, v1, v13
	ds_bpermute_b32 v13, v11, v1
	s_waitcnt lgkmcnt(0)
	v_add_f32_e32 v1, v1, v13
	ds_bpermute_b32 v13, v12, v1
	s_and_saveexec_b64 s[4:5], s[0:1]
	s_cbranch_execz .LBB0_484
	v_add_u32_e32 v14, 18, v0
	v_ashrrev_i32_e32 v15, 31, v14
	s_waitcnt lgkmcnt(0)
	v_add_f32_e32 v1, v1, v13
	v_lshl_add_u64 v[14:15], v[14:15], 2, s[30:31]
	global_store_dword v[14:15], v1, off sc1
.LBB0_484:
	s_or_b64 exec, exec, s[4:5]
	v_pk_mul_f32 v[14:15], v[40:41], v[40:41]
	s_nop 0
	v_add_f32_e32 v1, v15, v14
	v_fmac_f32_e32 v1, v19, v19
	v_fmac_f32_e32 v1, v7, v7
	s_waitcnt lgkmcnt(0)
	ds_bpermute_b32 v13, v2, v1
	s_waitcnt lgkmcnt(0)
	v_add_f32_e32 v1, v1, v13
	ds_bpermute_b32 v13, v3, v1
	s_waitcnt lgkmcnt(0)
	v_add_f32_e32 v1, v1, v13
	ds_bpermute_b32 v13, v10, v1
	s_waitcnt lgkmcnt(0)
	v_add_f32_e32 v1, v1, v13
	ds_bpermute_b32 v13, v11, v1
	s_waitcnt lgkmcnt(0)
	v_add_f32_e32 v1, v1, v13
	ds_bpermute_b32 v13, v12, v1
	s_and_saveexec_b64 s[4:5], s[0:1]
	s_cbranch_execz .LBB0_486
	v_add_u32_e32 v14, 19, v0
	v_ashrrev_i32_e32 v15, 31, v14
	s_waitcnt lgkmcnt(0)
	v_add_f32_e32 v1, v1, v13
	v_lshl_add_u64 v[14:15], v[14:15], 2, s[30:31]
	global_store_dword v[14:15], v1, off sc1
.LBB0_486:
	s_or_b64 exec, exec, s[4:5]
	v_pk_mul_f32 v[14:15], v[38:39], v[38:39]
	s_nop 0
	v_add_f32_e32 v1, v15, v14
	v_fmac_f32_e32 v1, v18, v18
	v_fmac_f32_e32 v1, v6, v6
	s_waitcnt lgkmcnt(0)
	ds_bpermute_b32 v13, v2, v1
	s_waitcnt lgkmcnt(0)
	v_add_f32_e32 v1, v1, v13
	ds_bpermute_b32 v13, v3, v1
	s_waitcnt lgkmcnt(0)
	v_add_f32_e32 v1, v1, v13
	ds_bpermute_b32 v13, v10, v1
	s_waitcnt lgkmcnt(0)
	v_add_f32_e32 v1, v1, v13
	ds_bpermute_b32 v13, v11, v1
	s_waitcnt lgkmcnt(0)
	v_add_f32_e32 v1, v1, v13
	ds_bpermute_b32 v13, v12, v1
	s_and_saveexec_b64 s[4:5], s[0:1]
	s_cbranch_execz .LBB0_488
	v_add_u32_e32 v14, 24, v0
	v_ashrrev_i32_e32 v15, 31, v14
	s_waitcnt lgkmcnt(0)
	v_add_f32_e32 v1, v1, v13
	v_lshl_add_u64 v[14:15], v[14:15], 2, s[30:31]
	global_store_dword v[14:15], v1, off sc1
.LBB0_488:
	s_or_b64 exec, exec, s[4:5]
	v_pk_mul_f32 v[14:15], v[36:37], v[36:37]
	s_nop 0
	v_add_f32_e32 v1, v15, v14
	v_fmac_f32_e32 v1, v17, v17
	v_fmac_f32_e32 v1, v5, v5
	s_waitcnt lgkmcnt(0)
	ds_bpermute_b32 v13, v2, v1
	s_waitcnt lgkmcnt(0)
	v_add_f32_e32 v1, v1, v13
	ds_bpermute_b32 v13, v3, v1
	s_waitcnt lgkmcnt(0)
	v_add_f32_e32 v1, v1, v13
	ds_bpermute_b32 v13, v10, v1
	s_waitcnt lgkmcnt(0)
	v_add_f32_e32 v1, v1, v13
	ds_bpermute_b32 v13, v11, v1
	s_waitcnt lgkmcnt(0)
	v_add_f32_e32 v1, v1, v13
	ds_bpermute_b32 v13, v12, v1
	s_and_saveexec_b64 s[4:5], s[0:1]
	s_cbranch_execz .LBB0_490
	v_add_u32_e32 v14, 25, v0
	v_ashrrev_i32_e32 v15, 31, v14
	s_waitcnt lgkmcnt(0)
	v_add_f32_e32 v1, v1, v13
	v_lshl_add_u64 v[14:15], v[14:15], 2, s[30:31]
	global_store_dword v[14:15], v1, off sc1
.LBB0_490:
	s_or_b64 exec, exec, s[4:5]
	v_pk_mul_f32 v[14:15], v[34:35], v[34:35]
	s_nop 0
	v_add_f32_e32 v1, v15, v14
	v_fmac_f32_e32 v1, v16, v16
	v_fmac_f32_e32 v1, v4, v4
	s_waitcnt lgkmcnt(0)
	ds_bpermute_b32 v13, v2, v1
	s_waitcnt lgkmcnt(0)
	v_add_f32_e32 v1, v1, v13
	ds_bpermute_b32 v13, v3, v1
	s_waitcnt lgkmcnt(0)
	v_add_f32_e32 v1, v1, v13
	ds_bpermute_b32 v13, v10, v1
	s_waitcnt lgkmcnt(0)
	v_add_f32_e32 v1, v1, v13
	ds_bpermute_b32 v13, v11, v1
	s_waitcnt lgkmcnt(0)
	v_add_f32_e32 v1, v1, v13
	ds_bpermute_b32 v13, v12, v1
	s_and_saveexec_b64 s[4:5], s[0:1]
	s_cbranch_execz .LBB0_492
	v_add_u32_e32 v14, 26, v0
	v_ashrrev_i32_e32 v15, 31, v14
	s_waitcnt lgkmcnt(0)
	v_add_f32_e32 v1, v1, v13
	v_lshl_add_u64 v[14:15], v[14:15], 2, s[30:31]
	global_store_dword v[14:15], v1, off sc1
.LBB0_492:
	s_or_b64 exec, exec, s[4:5]
	v_pk_mul_f32 v[14:15], v[32:33], v[32:33]
	s_nop 0
	v_add_f32_e32 v1, v15, v14
	v_fmac_f32_e32 v1, v82, v82
	v_fmac_f32_e32 v1, v83, v83
	ds_bpermute_b32 v2, v2, v1
	s_waitcnt lgkmcnt(0)
	v_add_f32_e32 v1, v1, v2
	ds_bpermute_b32 v2, v3, v1
	s_waitcnt lgkmcnt(0)
	v_add_f32_e32 v1, v1, v2
	ds_bpermute_b32 v2, v10, v1
	s_waitcnt lgkmcnt(0)
	v_add_f32_e32 v1, v1, v2
	ds_bpermute_b32 v2, v11, v1
	s_waitcnt lgkmcnt(0)
	v_add_f32_e32 v1, v1, v2
	ds_bpermute_b32 v2, v12, v1
	s_and_saveexec_b64 s[4:5], s[0:1]
	s_cbranch_execz .LBB0_494
	v_add_u32_e32 v0, 27, v0
	s_waitcnt lgkmcnt(0)
	v_add_f32_e32 v2, v1, v2
	v_ashrrev_i32_e32 v1, 31, v0
	v_lshl_add_u64 v[0:1], v[0:1], 2, s[30:31]
	global_store_dword v[0:1], v2, off sc1

.LBB0_497:
	v_mov_b32_e32 v0, s97
	ds_read_b64 v[0:1], v0
	s_waitcnt lgkmcnt(1)
	v_pk_mul_f32 v[2:3], v[78:79], v[78:79]
	v_or_b32_e32 v88, 32, v76
	v_or_b32_e32 v85, 64, v76
	v_or_b32_e32 v10, 0x60, v76
	s_waitcnt lgkmcnt(0)
	v_readfirstlane_b32 s4, v0
	v_readfirstlane_b32 s5, v1
	v_add_f32_e32 v2, v3, v2
	v_mov_b32_e32 v0, s4
	v_mov_b32_e32 v1, s5
	v_lshl_add_u64 v[0:1], v[76:77], 2, v[0:1]
	global_load_dword v77, v[0:1], off
	s_movk_i32 s4, 0x180
	v_fmac_f32_e32 v2, v57, v57
	v_fmac_f32_e32 v2, v56, v56
	s_waitcnt vmcnt(0)
	v_mul_f32_e32 v11, v79, v77
	v_cvt_pk_bf16_f32 v14, v11, s0
	v_mul_lo_u32 v11, v164, s4
	v_add_u32_e32 v12, v11, v76
	v_ashrrev_i32_e32 v13, 31, v12
	v_lshl_add_u64 v[12:13], v[12:13], 1, s[34:35]
	global_store_short v[12:13], v14, off sc1
	v_mul_f32_e32 v12, v75, v77
	v_cvt_pk_bf16_f32 v13, v12, s0
	v_add_u32_e32 v12, 0x180, v11
	v_add_u32_e32 v14, v12, v76
	v_ashrrev_i32_e32 v15, 31, v14
	v_lshl_add_u64 v[14:15], v[14:15], 1, s[34:35]
	global_store_short v[14:15], v13, off sc1
	v_mul_f32_e32 v13, v73, v77
	v_cvt_pk_bf16_f32 v58, v13, s0
	v_add_u32_e32 v13, 0x300, v11
	v_add_u32_e32 v14, v13, v76
	v_ashrrev_i32_e32 v15, 31, v14
	v_lshl_add_u64 v[14:15], v[14:15], 1, s[34:35]
	global_store_short v[14:15], v58, off sc1
	v_mul_f32_e32 v14, v71, v77
	v_cvt_pk_bf16_f32 v15, v14, s0
	v_add_u32_e32 v14, 0x480, v11
	v_add_u32_e32 v58, v14, v76
	v_ashrrev_i32_e32 v59, 31, v58
	v_lshl_add_u64 v[58:59], v[58:59], 1, s[34:35]
	global_store_short v[58:59], v15, off sc1
	v_mul_f32_e32 v15, v69, v77
	v_cvt_pk_bf16_f32 v60, v15, s0
	v_add_u32_e32 v15, 0xc00, v11
	v_add_u32_e32 v58, v15, v76
	v_ashrrev_i32_e32 v59, 31, v58
	v_lshl_add_u64 v[58:59], v[58:59], 1, s[34:35]
	global_store_short v[58:59], v60, off sc1
	v_mul_f32_e32 v58, v67, v77
	v_cvt_pk_bf16_f32 v59, v58, s0
	v_add_u32_e32 v58, 0xd80, v11
	v_add_u32_e32 v60, v58, v76
	v_ashrrev_i32_e32 v61, 31, v60
	v_lshl_add_u64 v[60:61], v[60:61], 1, s[34:35]
	global_store_short v[60:61], v59, off sc1
	v_mul_f32_e32 v59, v65, v77
	v_cvt_pk_bf16_f32 v62, v59, s0
	v_add_u32_e32 v59, 0xf00, v11
	v_add_u32_e32 v60, v59, v76
	v_ashrrev_i32_e32 v61, 31, v60
	v_lshl_add_u64 v[60:61], v[60:61], 1, s[34:35]
	global_store_short v[60:61], v62, off sc1
	v_mul_f32_e32 v60, v55, v77
	v_cvt_pk_bf16_f32 v61, v60, s0
	v_add_u32_e32 v60, 0x1080, v11
	v_add_u32_e32 v62, v60, v76
	v_ashrrev_i32_e32 v63, 31, v62
	v_lshl_add_u64 v[62:63], v[62:63], 1, s[34:35]
	global_store_short v[62:63], v61, off sc1
	v_mul_f32_e32 v61, v53, v77
	v_cvt_pk_bf16_f32 v79, v61, s0
	v_add_u32_e32 v61, 0x1800, v11
	v_add_u32_e32 v62, v61, v76
	v_ashrrev_i32_e32 v63, 31, v62
	v_lshl_add_u64 v[62:63], v[62:63], 1, s[34:35]
	global_store_short v[62:63], v79, off sc1
	v_mul_f32_e32 v62, v51, v77
	v_cvt_pk_bf16_f32 v63, v62, s0
	v_add_u32_e32 v62, 0x1980, v11
	v_add_u32_e32 v80, v62, v76
	v_ashrrev_i32_e32 v81, 31, v80
	v_lshl_add_u64 v[80:81], v[80:81], 1, s[34:35]
	global_store_short v[80:81], v63, off sc1
	v_mul_f32_e32 v63, v49, v77
	v_cvt_pk_bf16_f32 v79, v63, s0
	v_add_u32_e32 v63, 0x1b00, v11
	v_add_u32_e32 v80, v63, v76
	v_ashrrev_i32_e32 v81, 31, v80
	v_lshl_add_u64 v[80:81], v[80:81], 1, s[34:35]
	v_add_u32_e32 v84, 0x1c80, v11
	global_store_short v[80:81], v79, off sc1
	v_add_u32_e32 v80, v84, v76
	v_mul_f32_e32 v79, v41, v77
	v_ashrrev_i32_e32 v81, 31, v80
	v_cvt_pk_bf16_f32 v79, v79, s0
	v_lshl_add_u64 v[80:81], v[80:81], 1, s[34:35]
	global_store_short v[80:81], v79, off sc1
	v_add_u32_e32 v81, 0x2400, v11
	v_add_u32_e32 v86, v81, v76
	v_mul_f32_e32 v79, v39, v77
	v_ashrrev_i32_e32 v87, 31, v86
	v_cvt_pk_bf16_f32 v79, v79, s0
	v_lshl_add_u64 v[86:87], v[86:87], 1, s[34:35]
	v_add_u32_e32 v80, 0x2580, v11
	global_store_short v[86:87], v79, off sc1
	v_add_u32_e32 v86, v80, v76
	v_mul_f32_e32 v79, v37, v77
	v_ashrrev_i32_e32 v87, 31, v86
	v_cvt_pk_bf16_f32 v79, v79, s0
	v_lshl_add_u64 v[86:87], v[86:87], 1, s[34:35]
	global_store_short v[86:87], v79, off sc1
	v_mul_f32_e32 v79, v35, v77
	v_cvt_pk_bf16_f32 v89, v79, s0
	v_add_u32_e32 v79, 0x2700, v11
	v_add_u32_e32 v86, v79, v76
	v_ashrrev_i32_e32 v87, 31, v86
	v_lshl_add_u64 v[86:87], v[86:87], 1, s[34:35]
	v_mul_f32_e32 v77, v33, v77
	global_store_short v[86:87], v89, off sc1
	v_cvt_pk_bf16_f32 v89, v77, s0
	v_add_u32_e32 v77, 0x2880, v11
	v_add_u32_e32 v86, v77, v76
	global_load_dword v76, v[0:1], off offset:128
	v_ashrrev_i32_e32 v87, 31, v86
	v_lshl_add_u64 v[86:87], v[86:87], 1, s[34:35]
	global_store_short v[86:87], v89, off sc1
	v_add_u32_e32 v86, v11, v88
	v_ashrrev_i32_e32 v87, 31, v86
	v_lshl_add_u64 v[86:87], v[86:87], 1, s[34:35]
	s_waitcnt vmcnt(1)
	v_mul_f32_e32 v3, v78, v76
	v_cvt_pk_bf16_f32 v3, v3, s0
	global_store_short v[86:87], v3, off sc1
	v_add_u32_e32 v86, v12, v88
	v_mul_f32_e32 v3, v74, v76
	v_ashrrev_i32_e32 v87, 31, v86
	v_cvt_pk_bf16_f32 v3, v3, s0
	v_lshl_add_u64 v[86:87], v[86:87], 1, s[34:35]
	global_store_short v[86:87], v3, off sc1
	v_add_u32_e32 v86, v13, v88
	v_mul_f32_e32 v3, v72, v76
	v_ashrrev_i32_e32 v87, 31, v86
	v_cvt_pk_bf16_f32 v3, v3, s0
	v_lshl_add_u64 v[86:87], v[86:87], 1, s[34:35]
	global_store_short v[86:87], v3, off sc1
	v_add_u32_e32 v86, v14, v88
	v_mul_f32_e32 v3, v70, v76
	v_ashrrev_i32_e32 v87, 31, v86
	v_cvt_pk_bf16_f32 v3, v3, s0
	v_lshl_add_u64 v[86:87], v[86:87], 1, s[34:35]
	global_store_short v[86:87], v3, off sc1
	v_add_u32_e32 v86, v15, v88
	v_mul_f32_e32 v3, v68, v76
	v_ashrrev_i32_e32 v87, 31, v86
	v_cvt_pk_bf16_f32 v3, v3, s0
	v_lshl_add_u64 v[86:87], v[86:87], 1, s[34:35]
	global_store_short v[86:87], v3, off sc1
	v_add_u32_e32 v86, v58, v88
	v_mul_f32_e32 v3, v66, v76
	v_ashrrev_i32_e32 v87, 31, v86
	v_cvt_pk_bf16_f32 v3, v3, s0
	v_lshl_add_u64 v[86:87], v[86:87], 1, s[34:35]
	global_store_short v[86:87], v3, off sc1
	v_add_u32_e32 v86, v59, v88
	v_mul_f32_e32 v3, v64, v76
	v_ashrrev_i32_e32 v87, 31, v86
	v_cvt_pk_bf16_f32 v3, v3, s0
	v_lshl_add_u64 v[86:87], v[86:87], 1, s[34:35]
	global_store_short v[86:87], v3, off sc1
	v_add_u32_e32 v86, v60, v88
	v_mul_f32_e32 v3, v54, v76
	v_ashrrev_i32_e32 v87, 31, v86
	v_cvt_pk_bf16_f32 v3, v3, s0
	v_lshl_add_u64 v[86:87], v[86:87], 1, s[34:35]
	global_store_short v[86:87], v3, off sc1
	v_add_u32_e32 v86, v61, v88
	v_mul_f32_e32 v3, v52, v76
	v_ashrrev_i32_e32 v87, 31, v86
	v_cvt_pk_bf16_f32 v3, v3, s0
	v_lshl_add_u64 v[86:87], v[86:87], 1, s[34:35]
	global_store_short v[86:87], v3, off sc1
	v_add_u32_e32 v86, v62, v88
	v_mul_f32_e32 v3, v50, v76
	v_ashrrev_i32_e32 v87, 31, v86
	v_cvt_pk_bf16_f32 v3, v3, s0
	v_lshl_add_u64 v[86:87], v[86:87], 1, s[34:35]
	global_store_short v[86:87], v3, off sc1
	v_add_u32_e32 v86, v63, v88
	v_mul_f32_e32 v3, v48, v76
	v_ashrrev_i32_e32 v87, 31, v86
	v_cvt_pk_bf16_f32 v3, v3, s0
	v_lshl_add_u64 v[86:87], v[86:87], 1, s[34:35]
	global_store_short v[86:87], v3, off sc1
	v_add_u32_e32 v86, v84, v88
	v_mul_f32_e32 v3, v40, v76
	v_ashrrev_i32_e32 v87, 31, v86
	v_cvt_pk_bf16_f32 v3, v3, s0
	v_lshl_add_u64 v[86:87], v[86:87], 1, s[34:35]
	global_store_short v[86:87], v3, off sc1
	v_add_u32_e32 v86, v81, v88
	v_mul_f32_e32 v3, v38, v76
	v_ashrrev_i32_e32 v87, 31, v86
	v_cvt_pk_bf16_f32 v3, v3, s0
	v_lshl_add_u64 v[86:87], v[86:87], 1, s[34:35]
	global_store_short v[86:87], v3, off sc1
	v_add_u32_e32 v86, v80, v88
	v_mul_f32_e32 v3, v36, v76
	v_ashrrev_i32_e32 v87, 31, v86
	v_cvt_pk_bf16_f32 v3, v3, s0
	v_lshl_add_u64 v[86:87], v[86:87], 1, s[34:35]
	global_store_short v[86:87], v3, off sc1
	v_add_u32_e32 v86, v79, v88
	v_mul_f32_e32 v3, v34, v76
	v_ashrrev_i32_e32 v87, 31, v86
	v_cvt_pk_bf16_f32 v3, v3, s0
	v_lshl_add_u64 v[86:87], v[86:87], 1, s[34:35]
	global_store_short v[86:87], v3, off sc1
	v_add_u32_e32 v86, v77, v88
	v_mul_f32_e32 v3, v32, v76
	v_ashrrev_i32_e32 v87, 31, v86
	v_cvt_pk_bf16_f32 v3, v3, s0
	v_lshl_add_u64 v[86:87], v[86:87], 1, s[34:35]
	global_store_short v[86:87], v3, off sc1
	global_load_dword v3, v[0:1], off offset:256
	v_add_u32_e32 v86, v11, v85
	v_ashrrev_i32_e32 v87, 31, v86
	v_lshl_add_u64 v[86:87], v[86:87], 1, s[34:35]
	s_waitcnt vmcnt(0)
	v_mul_f32_e32 v57, v57, v3
	v_cvt_pk_bf16_f32 v57, v57, s0
	global_store_short v[86:87], v57, off sc1
	v_add_u32_e32 v86, v12, v85
	v_mul_f32_e32 v57, v47, v3
	v_ashrrev_i32_e32 v87, 31, v86
	v_cvt_pk_bf16_f32 v57, v57, s0
	v_lshl_add_u64 v[86:87], v[86:87], 1, s[34:35]
	global_store_short v[86:87], v57, off sc1
	v_add_u32_e32 v86, v13, v85
	v_mul_f32_e32 v57, v46, v3
	v_ashrrev_i32_e32 v87, 31, v86
	v_cvt_pk_bf16_f32 v57, v57, s0
	v_lshl_add_u64 v[86:87], v[86:87], 1, s[34:35]
	global_store_short v[86:87], v57, off sc1
	v_add_u32_e32 v86, v14, v85
	v_mul_f32_e32 v57, v45, v3
	v_ashrrev_i32_e32 v87, 31, v86
	v_cvt_pk_bf16_f32 v57, v57, s0
	v_lshl_add_u64 v[86:87], v[86:87], 1, s[34:35]
	global_store_short v[86:87], v57, off sc1
	v_add_u32_e32 v86, v15, v85
	v_mul_f32_e32 v57, v44, v3
	v_ashrrev_i32_e32 v87, 31, v86
	v_cvt_pk_bf16_f32 v57, v57, s0
	v_lshl_add_u64 v[86:87], v[86:87], 1, s[34:35]
	global_store_short v[86:87], v57, off sc1
	v_add_u32_e32 v86, v58, v85
	v_mul_f32_e32 v57, v43, v3
	v_ashrrev_i32_e32 v87, 31, v86
	v_cvt_pk_bf16_f32 v57, v57, s0
	v_lshl_add_u64 v[86:87], v[86:87], 1, s[34:35]
	global_store_short v[86:87], v57, off sc1
	v_add_u32_e32 v86, v59, v85
	v_mul_f32_e32 v57, v42, v3
	v_ashrrev_i32_e32 v87, 31, v86
	v_cvt_pk_bf16_f32 v57, v57, s0
	v_lshl_add_u64 v[86:87], v[86:87], 1, s[34:35]
	global_store_short v[86:87], v57, off sc1
	v_add_u32_e32 v86, v60, v85
	v_mul_f32_e32 v57, v23, v3
	v_ashrrev_i32_e32 v87, 31, v86
	v_cvt_pk_bf16_f32 v57, v57, s0
	v_lshl_add_u64 v[86:87], v[86:87], 1, s[34:35]
	global_store_short v[86:87], v57, off sc1
	v_add_u32_e32 v86, v61, v85
	v_mul_f32_e32 v57, v22, v3
	v_ashrrev_i32_e32 v87, 31, v86
	v_cvt_pk_bf16_f32 v57, v57, s0
	v_lshl_add_u64 v[86:87], v[86:87], 1, s[34:35]
	global_store_short v[86:87], v57, off sc1
	v_add_u32_e32 v86, v62, v85
	v_mul_f32_e32 v57, v21, v3
	v_ashrrev_i32_e32 v87, 31, v86
	v_cvt_pk_bf16_f32 v57, v57, s0
	v_lshl_add_u64 v[86:87], v[86:87], 1, s[34:35]
	global_store_short v[86:87], v57, off sc1
	v_add_u32_e32 v86, v63, v85
	v_mul_f32_e32 v57, v20, v3
	v_ashrrev_i32_e32 v87, 31, v86
	v_cvt_pk_bf16_f32 v57, v57, s0
	v_lshl_add_u64 v[86:87], v[86:87], 1, s[34:35]
	global_store_short v[86:87], v57, off sc1
	v_add_u32_e32 v86, v84, v85
	v_mul_f32_e32 v57, v19, v3
	v_ashrrev_i32_e32 v87, 31, v86
	v_cvt_pk_bf16_f32 v57, v57, s0
	v_lshl_add_u64 v[86:87], v[86:87], 1, s[34:35]
	global_store_short v[86:87], v57, off sc1
	v_add_u32_e32 v86, v81, v85
	v_mul_f32_e32 v57, v18, v3
	v_ashrrev_i32_e32 v87, 31, v86
	v_cvt_pk_bf16_f32 v57, v57, s0
	v_lshl_add_u64 v[86:87], v[86:87], 1, s[34:35]
	global_store_short v[86:87], v57, off sc1
	v_add_u32_e32 v86, v80, v85
	v_mul_f32_e32 v57, v17, v3
	v_ashrrev_i32_e32 v87, 31, v86
	v_cvt_pk_bf16_f32 v57, v57, s0
	v_lshl_add_u64 v[86:87], v[86:87], 1, s[34:35]
	global_store_short v[86:87], v57, off sc1
	v_add_u32_e32 v86, v79, v85
	v_mul_f32_e32 v57, v16, v3
	v_ashrrev_i32_e32 v87, 31, v86
	v_cvt_pk_bf16_f32 v57, v57, s0
	v_lshl_add_u64 v[86:87], v[86:87], 1, s[34:35]
	global_store_short v[86:87], v57, off sc1
	v_add_u32_e32 v86, v77, v85
	v_mul_f32_e32 v3, v82, v3
	v_ashrrev_i32_e32 v87, 31, v86
	v_cvt_pk_bf16_f32 v3, v3, s0
	v_lshl_add_u64 v[86:87], v[86:87], 1, s[34:35]
	global_store_short v[86:87], v3, off sc1
	global_load_dword v3, v[0:1], off offset:384
	s_waitcnt vmcnt(0)
	v_mul_f32_e32 v0, v56, v3
	v_cvt_pk_bf16_f32 v56, v0, s0
	v_add_u32_e32 v0, v11, v10
	v_ashrrev_i32_e32 v1, 31, v0
	v_lshl_add_u64 v[0:1], v[0:1], 1, s[34:35]
	global_store_short v[0:1], v56, off sc1
	v_mul_f32_e32 v0, v31, v3
	v_cvt_pk_bf16_f32 v11, v0, s0
	v_add_u32_e32 v0, v12, v10
	v_ashrrev_i32_e32 v1, 31, v0
	v_lshl_add_u64 v[0:1], v[0:1], 1, s[34:35]
	global_store_short v[0:1], v11, off sc1
	v_mul_f32_e32 v0, v30, v3
	v_cvt_pk_bf16_f32 v11, v0, s0
	v_add_u32_e32 v0, v13, v10
	v_ashrrev_i32_e32 v1, 31, v0
	v_lshl_add_u64 v[0:1], v[0:1], 1, s[34:35]
	global_store_short v[0:1], v11, off sc1
	v_mul_f32_e32 v0, v29, v3
	v_cvt_pk_bf16_f32 v11, v0, s0
	v_add_u32_e32 v0, v14, v10
	v_ashrrev_i32_e32 v1, 31, v0
	v_lshl_add_u64 v[0:1], v[0:1], 1, s[34:35]
	global_store_short v[0:1], v11, off sc1
	v_mul_f32_e32 v0, v28, v3
	v_cvt_pk_bf16_f32 v11, v0, s0
	v_add_u32_e32 v0, v15, v10
	v_ashrrev_i32_e32 v1, 31, v0
	v_lshl_add_u64 v[0:1], v[0:1], 1, s[34:35]
	global_store_short v[0:1], v11, off sc1
	v_mul_f32_e32 v0, v27, v3
	v_cvt_pk_bf16_f32 v11, v0, s0
	v_add_u32_e32 v0, v58, v10
	v_ashrrev_i32_e32 v1, 31, v0
	v_lshl_add_u64 v[0:1], v[0:1], 1, s[34:35]
	global_store_short v[0:1], v11, off sc1
	v_mul_f32_e32 v0, v26, v3
	v_cvt_pk_bf16_f32 v11, v0, s0
	v_add_u32_e32 v0, v59, v10
	v_ashrrev_i32_e32 v1, 31, v0
	v_lshl_add_u64 v[0:1], v[0:1], 1, s[34:35]
	global_store_short v[0:1], v11, off sc1
	v_mul_f32_e32 v0, v25, v3
	v_cvt_pk_bf16_f32 v11, v0, s0
	v_add_u32_e32 v0, v60, v10
	v_ashrrev_i32_e32 v1, 31, v0
	v_lshl_add_u64 v[0:1], v[0:1], 1, s[34:35]
	global_store_short v[0:1], v11, off sc1
	v_mul_f32_e32 v0, v24, v3
	v_cvt_pk_bf16_f32 v11, v0, s0
	v_add_u32_e32 v0, v61, v10
	v_ashrrev_i32_e32 v1, 31, v0
	v_lshl_add_u64 v[0:1], v[0:1], 1, s[34:35]
	global_store_short v[0:1], v11, off sc1
	v_mul_f32_e32 v0, v9, v3
	v_cvt_pk_bf16_f32 v11, v0, s0
	v_add_u32_e32 v0, v62, v10
	v_ashrrev_i32_e32 v1, 31, v0
	v_lshl_add_u64 v[0:1], v[0:1], 1, s[34:35]
	global_store_short v[0:1], v11, off sc1
	v_mul_f32_e32 v0, v8, v3
	v_cvt_pk_bf16_f32 v11, v0, s0
	v_add_u32_e32 v0, v63, v10
	v_ashrrev_i32_e32 v1, 31, v0
	v_lshl_add_u64 v[0:1], v[0:1], 1, s[34:35]
	global_store_short v[0:1], v11, off sc1
	v_mul_f32_e32 v0, v7, v3
	v_cvt_pk_bf16_f32 v11, v0, s0
	v_add_u32_e32 v0, v84, v10
	v_ashrrev_i32_e32 v1, 31, v0
	v_lshl_add_u64 v[0:1], v[0:1], 1, s[34:35]
	global_store_short v[0:1], v11, off sc1
	v_mul_f32_e32 v0, v6, v3
	v_cvt_pk_bf16_f32 v11, v0, s0
	v_add_u32_e32 v0, v81, v10
	v_ashrrev_i32_e32 v1, 31, v0
	v_lshl_add_u64 v[0:1], v[0:1], 1, s[34:35]
	global_store_short v[0:1], v11, off sc1
	v_mul_f32_e32 v0, v5, v3
	v_cvt_pk_bf16_f32 v11, v0, s0
	v_add_u32_e32 v0, v80, v10
	v_ashrrev_i32_e32 v1, 31, v0
	v_lshl_add_u64 v[0:1], v[0:1], 1, s[34:35]
	global_store_short v[0:1], v11, off sc1
	v_mul_f32_e32 v0, v4, v3
	v_cvt_pk_bf16_f32 v11, v0, s0
	v_add_u32_e32 v0, v79, v10
	v_ashrrev_i32_e32 v1, 31, v0
	v_lshl_add_u64 v[0:1], v[0:1], 1, s[34:35]
	global_store_short v[0:1], v11, off sc1
	v_mul_f32_e32 v0, v83, v3
	v_cvt_pk_bf16_f32 v3, v0, s0
	v_add_u32_e32 v0, v77, v10
	v_ashrrev_i32_e32 v1, 31, v0
	v_lshl_add_u64 v[0:1], v[0:1], 1, s[34:35]
	global_store_short v[0:1], v3, off sc1
	v_and_b32_e32 v1, 64, v214
	v_xor_b32_e32 v0, 1, v214
	v_add_u32_e32 v1, 64, v1
	v_cmp_lt_i32_e32 vcc, v0, v1
	s_nop 1
	v_cndmask_b32_e32 v0, v214, v0, vcc
	v_lshlrev_b32_e32 v3, 2, v0
	v_xor_b32_e32 v0, 2, v214
	v_cmp_lt_i32_e32 vcc, v0, v1
	s_nop 1
	v_cndmask_b32_e32 v0, v214, v0, vcc
	v_lshlrev_b32_e32 v10, 2, v0
	v_xor_b32_e32 v0, 4, v214
	v_cmp_lt_i32_e32 vcc, v0, v1
	s_nop 1
	v_cndmask_b32_e32 v0, v214, v0, vcc
	v_lshlrev_b32_e32 v11, 2, v0
	v_xor_b32_e32 v0, 8, v214
	v_cmp_lt_i32_e32 vcc, v0, v1
	s_nop 1
	v_cndmask_b32_e32 v0, v214, v0, vcc
	v_lshlrev_b32_e32 v12, 2, v0
	v_xor_b32_e32 v0, 16, v214
	v_cmp_lt_i32_e32 vcc, v0, v1
	ds_bpermute_b32 v1, v3, v2
	s_waitcnt lgkmcnt(0)
	v_add_f32_e32 v1, v2, v1
	ds_bpermute_b32 v2, v10, v1
	v_cndmask_b32_e32 v0, v214, v0, vcc
	v_lshlrev_b32_e32 v13, 2, v0
	v_lshl_add_u32 v0, s10, 14, v164
	s_waitcnt lgkmcnt(0)
	v_add_f32_e32 v1, v1, v2
	ds_bpermute_b32 v2, v11, v1
	s_waitcnt lgkmcnt(0)
	v_add_f32_e32 v1, v1, v2
	ds_bpermute_b32 v2, v12, v1
	s_waitcnt lgkmcnt(0)
	v_add_f32_e32 v2, v1, v2
	ds_bpermute_b32 v14, v13, v2
	v_ashrrev_i32_e32 v1, 31, v0
	s_and_saveexec_b64 s[4:5], s[0:1]
	s_cbranch_execz .LBB0_499
	s_waitcnt lgkmcnt(0)
	v_add_f32_e32 v2, v2, v14
	v_lshl_add_u64 v[14:15], v[0:1], 2, s[36:37]
	global_store_dword v[14:15], v2, off sc1
.LBB0_499:
	s_or_b64 exec, exec, s[4:5]
	s_waitcnt lgkmcnt(0)
	v_pk_mul_f32 v[14:15], v[74:75], v[74:75]
	s_nop 0
	v_add_f32_e32 v2, v15, v14
	v_fmac_f32_e32 v2, v47, v47
	v_fmac_f32_e32 v2, v31, v31
	ds_bpermute_b32 v14, v3, v2
	s_waitcnt lgkmcnt(0)
	v_add_f32_e32 v2, v2, v14
	ds_bpermute_b32 v14, v10, v2
	s_waitcnt lgkmcnt(0)
	v_add_f32_e32 v2, v2, v14
	ds_bpermute_b32 v14, v11, v2
	s_waitcnt lgkmcnt(0)
	v_add_f32_e32 v2, v2, v14
	ds_bpermute_b32 v14, v12, v2
	s_waitcnt lgkmcnt(0)
	v_add_f32_e32 v2, v2, v14
	ds_bpermute_b32 v14, v13, v2
	s_and_saveexec_b64 s[4:5], s[0:1]
	s_cbranch_execz .LBB0_501
	s_waitcnt lgkmcnt(0)
	v_add_f32_e32 v2, v2, v14
	v_lshl_add_u64 v[14:15], v[0:1], 2, s[36:37]
	global_store_dword v[14:15], v2, off offset:4 sc1
.LBB0_501:
	s_or_b64 exec, exec, s[4:5]
	s_waitcnt lgkmcnt(0)
	v_pk_mul_f32 v[14:15], v[72:73], v[72:73]
	s_nop 0
	v_add_f32_e32 v2, v15, v14
	v_fmac_f32_e32 v2, v46, v46
	v_fmac_f32_e32 v2, v30, v30
	ds_bpermute_b32 v14, v3, v2
	s_waitcnt lgkmcnt(0)
	v_add_f32_e32 v2, v2, v14
	ds_bpermute_b32 v14, v10, v2
	s_waitcnt lgkmcnt(0)
	v_add_f32_e32 v2, v2, v14
	ds_bpermute_b32 v14, v11, v2
	s_waitcnt lgkmcnt(0)
	v_add_f32_e32 v2, v2, v14
	ds_bpermute_b32 v14, v12, v2
	s_waitcnt lgkmcnt(0)
	v_add_f32_e32 v2, v2, v14
	ds_bpermute_b32 v14, v13, v2
	s_and_saveexec_b64 s[4:5], s[0:1]
	s_cbranch_execz .LBB0_503
	s_waitcnt lgkmcnt(0)
	v_add_f32_e32 v2, v2, v14
	v_lshl_add_u64 v[14:15], v[0:1], 2, s[36:37]
	global_store_dword v[14:15], v2, off offset:8 sc1
.LBB0_503:
	s_or_b64 exec, exec, s[4:5]
	s_waitcnt lgkmcnt(0)
	v_pk_mul_f32 v[14:15], v[70:71], v[70:71]
	s_nop 0
	v_add_f32_e32 v2, v15, v14
	v_fmac_f32_e32 v2, v45, v45
	v_fmac_f32_e32 v2, v29, v29
	ds_bpermute_b32 v14, v3, v2
	s_waitcnt lgkmcnt(0)
	v_add_f32_e32 v2, v2, v14
	ds_bpermute_b32 v14, v10, v2
	s_waitcnt lgkmcnt(0)
	v_add_f32_e32 v2, v2, v14
	ds_bpermute_b32 v14, v11, v2
	s_waitcnt lgkmcnt(0)
	v_add_f32_e32 v2, v2, v14
	ds_bpermute_b32 v14, v12, v2
	s_waitcnt lgkmcnt(0)
	v_add_f32_e32 v2, v2, v14
	ds_bpermute_b32 v14, v13, v2
	s_and_saveexec_b64 s[4:5], s[0:1]
	s_cbranch_execz .LBB0_505
	s_waitcnt lgkmcnt(0)
	v_add_f32_e32 v2, v2, v14
	v_lshl_add_u64 v[14:15], v[0:1], 2, s[36:37]
	global_store_dword v[14:15], v2, off offset:12 sc1
.LBB0_505:
	s_or_b64 exec, exec, s[4:5]
	s_waitcnt lgkmcnt(0)
	v_pk_mul_f32 v[14:15], v[68:69], v[68:69]
	s_nop 0
	v_add_f32_e32 v2, v15, v14
	v_fmac_f32_e32 v2, v44, v44
	v_fmac_f32_e32 v2, v28, v28
	ds_bpermute_b32 v14, v3, v2
	s_waitcnt lgkmcnt(0)
	v_add_f32_e32 v2, v2, v14
	ds_bpermute_b32 v14, v10, v2
	s_waitcnt lgkmcnt(0)
	v_add_f32_e32 v2, v2, v14
	ds_bpermute_b32 v14, v11, v2
	s_waitcnt lgkmcnt(0)
	v_add_f32_e32 v2, v2, v14
	ds_bpermute_b32 v14, v12, v2
	s_waitcnt lgkmcnt(0)
	v_add_f32_e32 v2, v2, v14
	ds_bpermute_b32 v14, v13, v2
	s_and_saveexec_b64 s[4:5], s[0:1]
	s_cbranch_execz .LBB0_507
	s_waitcnt lgkmcnt(0)
	v_add_f32_e32 v2, v2, v14
	v_lshl_add_u64 v[14:15], v[0:1], 2, s[36:37]
	global_store_dword v[14:15], v2, off offset:32 sc1
.LBB0_507:
	s_or_b64 exec, exec, s[4:5]
	s_waitcnt lgkmcnt(0)
	v_pk_mul_f32 v[14:15], v[66:67], v[66:67]
	s_nop 0
	v_add_f32_e32 v2, v15, v14
	v_fmac_f32_e32 v2, v43, v43
	v_fmac_f32_e32 v2, v27, v27
	ds_bpermute_b32 v14, v3, v2
	s_waitcnt lgkmcnt(0)
	v_add_f32_e32 v2, v2, v14
	ds_bpermute_b32 v14, v10, v2
	s_waitcnt lgkmcnt(0)
	v_add_f32_e32 v2, v2, v14
	ds_bpermute_b32 v14, v11, v2
	s_waitcnt lgkmcnt(0)
	v_add_f32_e32 v2, v2, v14
	ds_bpermute_b32 v14, v12, v2
	s_waitcnt lgkmcnt(0)
	v_add_f32_e32 v2, v2, v14
	ds_bpermute_b32 v14, v13, v2
	s_and_saveexec_b64 s[4:5], s[0:1]
	s_cbranch_execz .LBB0_509
	s_waitcnt lgkmcnt(0)
	v_add_f32_e32 v2, v2, v14
	v_lshl_add_u64 v[14:15], v[0:1], 2, s[36:37]
	global_store_dword v[14:15], v2, off offset:36 sc1
.LBB0_509:
	s_or_b64 exec, exec, s[4:5]
	s_waitcnt lgkmcnt(0)
	v_pk_mul_f32 v[14:15], v[64:65], v[64:65]
	s_nop 0
	v_add_f32_e32 v2, v15, v14
	v_fmac_f32_e32 v2, v42, v42
	v_fmac_f32_e32 v2, v26, v26
	ds_bpermute_b32 v14, v3, v2
	s_waitcnt lgkmcnt(0)
	v_add_f32_e32 v2, v2, v14
	ds_bpermute_b32 v14, v10, v2
	s_waitcnt lgkmcnt(0)
	v_add_f32_e32 v2, v2, v14
	ds_bpermute_b32 v14, v11, v2
	s_waitcnt lgkmcnt(0)
	v_add_f32_e32 v2, v2, v14
	ds_bpermute_b32 v14, v12, v2
	s_waitcnt lgkmcnt(0)
	v_add_f32_e32 v2, v2, v14
	ds_bpermute_b32 v14, v13, v2
	s_and_saveexec_b64 s[4:5], s[0:1]
	s_cbranch_execz .LBB0_511
	s_waitcnt lgkmcnt(0)
	v_add_f32_e32 v2, v2, v14
	v_lshl_add_u64 v[14:15], v[0:1], 2, s[36:37]
	global_store_dword v[14:15], v2, off offset:40 sc1
.LBB0_511:
	s_or_b64 exec, exec, s[4:5]
	s_waitcnt lgkmcnt(0)
	v_pk_mul_f32 v[14:15], v[54:55], v[54:55]
	s_nop 0
	v_add_f32_e32 v2, v15, v14
	v_fmac_f32_e32 v2, v23, v23
	v_fmac_f32_e32 v2, v25, v25
	ds_bpermute_b32 v14, v3, v2
	s_waitcnt lgkmcnt(0)
	v_add_f32_e32 v2, v2, v14
	ds_bpermute_b32 v14, v10, v2
	s_waitcnt lgkmcnt(0)
	v_add_f32_e32 v2, v2, v14
	ds_bpermute_b32 v14, v11, v2
	s_waitcnt lgkmcnt(0)
	v_add_f32_e32 v2, v2, v14
	ds_bpermute_b32 v14, v12, v2
	s_waitcnt lgkmcnt(0)
	v_add_f32_e32 v2, v2, v14
	ds_bpermute_b32 v14, v13, v2
	s_and_saveexec_b64 s[4:5], s[0:1]
	s_cbranch_execz .LBB0_513
	s_waitcnt lgkmcnt(0)
	v_add_f32_e32 v2, v2, v14
	v_lshl_add_u64 v[14:15], v[0:1], 2, s[36:37]
	global_store_dword v[14:15], v2, off offset:44 sc1
.LBB0_513:
	s_or_b64 exec, exec, s[4:5]
	s_waitcnt lgkmcnt(0)
	v_pk_mul_f32 v[14:15], v[52:53], v[52:53]
	s_nop 0
	v_add_f32_e32 v2, v15, v14
	v_fmac_f32_e32 v2, v22, v22
	v_fmac_f32_e32 v2, v24, v24
	ds_bpermute_b32 v14, v3, v2
	s_waitcnt lgkmcnt(0)
	v_add_f32_e32 v2, v2, v14
	ds_bpermute_b32 v14, v10, v2
	s_waitcnt lgkmcnt(0)
	v_add_f32_e32 v2, v2, v14
	ds_bpermute_b32 v14, v11, v2
	s_waitcnt lgkmcnt(0)
	v_add_f32_e32 v2, v2, v14
	ds_bpermute_b32 v14, v12, v2
	s_waitcnt lgkmcnt(0)
	v_add_f32_e32 v2, v2, v14
	ds_bpermute_b32 v14, v13, v2
	s_and_saveexec_b64 s[4:5], s[0:1]
	s_cbranch_execz .LBB0_515
	s_waitcnt lgkmcnt(0)
	v_add_f32_e32 v2, v2, v14
	v_lshl_add_u64 v[14:15], v[0:1], 2, s[36:37]
	global_store_dword v[14:15], v2, off offset:64 sc1
.LBB0_515:
	s_or_b64 exec, exec, s[4:5]
	s_waitcnt lgkmcnt(0)
	v_pk_mul_f32 v[14:15], v[50:51], v[50:51]
	s_nop 0
	v_add_f32_e32 v2, v15, v14
	v_fmac_f32_e32 v2, v21, v21
	v_fmac_f32_e32 v2, v9, v9
	ds_bpermute_b32 v9, v3, v2
	s_waitcnt lgkmcnt(0)
	v_add_f32_e32 v2, v2, v9
	ds_bpermute_b32 v9, v10, v2
	s_waitcnt lgkmcnt(0)
	v_add_f32_e32 v2, v2, v9
	ds_bpermute_b32 v9, v11, v2
	s_waitcnt lgkmcnt(0)
	v_add_f32_e32 v2, v2, v9
	ds_bpermute_b32 v9, v12, v2
	s_waitcnt lgkmcnt(0)
	v_add_f32_e32 v2, v2, v9
	ds_bpermute_b32 v9, v13, v2
	s_and_saveexec_b64 s[4:5], s[0:1]
	s_cbranch_execz .LBB0_517
	s_waitcnt lgkmcnt(0)
	v_add_f32_e32 v2, v2, v9
	v_lshl_add_u64 v[14:15], v[0:1], 2, s[36:37]
	global_store_dword v[14:15], v2, off offset:68 sc1
.LBB0_517:
	s_or_b64 exec, exec, s[4:5]
	v_pk_mul_f32 v[14:15], v[48:49], v[48:49]
	s_nop 0
	v_add_f32_e32 v2, v15, v14
	v_fmac_f32_e32 v2, v20, v20
	v_fmac_f32_e32 v2, v8, v8
	ds_bpermute_b32 v8, v3, v2
	s_waitcnt lgkmcnt(0)
	v_add_f32_e32 v2, v2, v8
	ds_bpermute_b32 v8, v10, v2
	s_waitcnt lgkmcnt(0)
	v_add_f32_e32 v2, v2, v8
	ds_bpermute_b32 v8, v11, v2
	s_waitcnt lgkmcnt(0)
	v_add_f32_e32 v2, v2, v8
	ds_bpermute_b32 v8, v12, v2
	s_waitcnt lgkmcnt(0)
	v_add_f32_e32 v2, v2, v8
	ds_bpermute_b32 v8, v13, v2
	s_and_saveexec_b64 s[4:5], s[0:1]
	s_cbranch_execz .LBB0_519
	s_waitcnt lgkmcnt(0)
	v_add_f32_e32 v2, v2, v8
	v_lshl_add_u64 v[8:9], v[0:1], 2, s[36:37]
	global_store_dword v[8:9], v2, off offset:72 sc1
.LBB0_519:
	s_or_b64 exec, exec, s[4:5]
	s_waitcnt lgkmcnt(0)
	v_pk_mul_f32 v[8:9], v[40:41], v[40:41]
	s_nop 0
	v_add_f32_e32 v2, v9, v8
	v_fmac_f32_e32 v2, v19, v19
	v_fmac_f32_e32 v2, v7, v7
	ds_bpermute_b32 v7, v3, v2
	s_waitcnt lgkmcnt(0)
	v_add_f32_e32 v2, v2, v7
	ds_bpermute_b32 v7, v10, v2
	s_waitcnt lgkmcnt(0)
	v_add_f32_e32 v2, v2, v7
	ds_bpermute_b32 v7, v11, v2
	s_waitcnt lgkmcnt(0)
	v_add_f32_e32 v2, v2, v7
	ds_bpermute_b32 v7, v12, v2
	s_waitcnt lgkmcnt(0)
	v_add_f32_e32 v2, v2, v7
	ds_bpermute_b32 v7, v13, v2
	s_and_saveexec_b64 s[4:5], s[0:1]
	s_cbranch_execz .LBB0_521
	s_waitcnt lgkmcnt(0)
	v_add_f32_e32 v2, v2, v7
	v_lshl_add_u64 v[8:9], v[0:1], 2, s[36:37]
	global_store_dword v[8:9], v2, off offset:76 sc1
.LBB0_521:
	s_or_b64 exec, exec, s[4:5]
	v_pk_mul_f32 v[8:9], v[38:39], v[38:39]
	s_nop 0
	v_add_f32_e32 v2, v9, v8
	v_fmac_f32_e32 v2, v18, v18
	v_fmac_f32_e32 v2, v6, v6
	ds_bpermute_b32 v6, v3, v2
	s_waitcnt lgkmcnt(0)
	v_add_f32_e32 v2, v2, v6
	ds_bpermute_b32 v6, v10, v2
	s_waitcnt lgkmcnt(0)
	v_add_f32_e32 v2, v2, v6
	ds_bpermute_b32 v6, v11, v2
	s_waitcnt lgkmcnt(0)
	v_add_f32_e32 v2, v2, v6
	ds_bpermute_b32 v6, v12, v2
	s_waitcnt lgkmcnt(0)
	v_add_f32_e32 v2, v2, v6
	ds_bpermute_b32 v6, v13, v2
	s_and_saveexec_b64 s[4:5], s[0:1]
	s_cbranch_execz .LBB0_523
	s_waitcnt lgkmcnt(0)
	v_add_f32_e32 v2, v2, v6
	v_lshl_add_u64 v[6:7], v[0:1], 2, s[36:37]
	global_store_dword v[6:7], v2, off offset:96 sc1
.LBB0_523:
	s_or_b64 exec, exec, s[4:5]
	s_waitcnt lgkmcnt(0)
	v_pk_mul_f32 v[6:7], v[36:37], v[36:37]
	s_nop 0
	v_add_f32_e32 v2, v7, v6
	v_fmac_f32_e32 v2, v17, v17
	v_fmac_f32_e32 v2, v5, v5
	ds_bpermute_b32 v5, v3, v2
	s_waitcnt lgkmcnt(0)
	v_add_f32_e32 v2, v2, v5
	ds_bpermute_b32 v5, v10, v2
	s_waitcnt lgkmcnt(0)
	v_add_f32_e32 v2, v2, v5
	ds_bpermute_b32 v5, v11, v2
	s_waitcnt lgkmcnt(0)
	v_add_f32_e32 v2, v2, v5
	ds_bpermute_b32 v5, v12, v2
	s_waitcnt lgkmcnt(0)
	v_add_f32_e32 v2, v2, v5
	ds_bpermute_b32 v5, v13, v2
	s_and_saveexec_b64 s[4:5], s[0:1]
	s_cbranch_execz .LBB0_525
	s_waitcnt lgkmcnt(0)
	v_add_f32_e32 v2, v2, v5
	v_lshl_add_u64 v[6:7], v[0:1], 2, s[36:37]
	global_store_dword v[6:7], v2, off offset:100 sc1
.LBB0_525:
	s_or_b64 exec, exec, s[4:5]
	v_pk_mul_f32 v[6:7], v[34:35], v[34:35]
	s_nop 0
	v_add_f32_e32 v2, v7, v6
	v_fmac_f32_e32 v2, v16, v16
	v_fmac_f32_e32 v2, v4, v4
	ds_bpermute_b32 v4, v3, v2
	s_waitcnt lgkmcnt(0)
	v_add_f32_e32 v2, v2, v4
	ds_bpermute_b32 v4, v10, v2
	s_waitcnt lgkmcnt(0)
	v_add_f32_e32 v2, v2, v4
	ds_bpermute_b32 v4, v11, v2
	s_waitcnt lgkmcnt(0)
	v_add_f32_e32 v2, v2, v4
	ds_bpermute_b32 v4, v12, v2
	s_waitcnt lgkmcnt(0)
	v_add_f32_e32 v2, v2, v4
	ds_bpermute_b32 v4, v13, v2
	s_and_saveexec_b64 s[4:5], s[0:1]
	s_cbranch_execz .LBB0_527
	s_waitcnt lgkmcnt(0)
	v_add_f32_e32 v2, v2, v4
	v_lshl_add_u64 v[4:5], v[0:1], 2, s[36:37]
	global_store_dword v[4:5], v2, off offset:104 sc1
.LBB0_527:
	s_or_b64 exec, exec, s[4:5]
	s_waitcnt lgkmcnt(0)
	v_pk_mul_f32 v[4:5], v[32:33], v[32:33]
	s_nop 0
	v_add_f32_e32 v2, v5, v4
	v_fmac_f32_e32 v2, v82, v82
	v_fmac_f32_e32 v2, v83, v83
	ds_bpermute_b32 v3, v3, v2
	s_waitcnt lgkmcnt(0)
	v_add_f32_e32 v2, v2, v3
	ds_bpermute_b32 v3, v10, v2
	s_waitcnt lgkmcnt(0)
	v_add_f32_e32 v2, v2, v3
	ds_bpermute_b32 v3, v11, v2
	s_waitcnt lgkmcnt(0)
	v_add_f32_e32 v2, v2, v3
	ds_bpermute_b32 v3, v12, v2
	s_waitcnt lgkmcnt(0)
	v_add_f32_e32 v2, v2, v3
	ds_bpermute_b32 v3, v13, v2
	s_and_saveexec_b64 s[4:5], s[0:1]
	s_cbranch_execz .LBB0_256
	s_waitcnt lgkmcnt(0)
	v_add_f32_e32 v2, v2, v3
	v_lshl_add_u64 v[0:1], v[0:1], 2, s[36:37]
	global_store_dword v[0:1], v2, off offset:108 sc1
	s_branch .LBB0_256

.LBB0_532:
	v_lshrrev_b32_e32 v16, 9, v6
	v_ashrrev_i32_e32 v17, 17, v6
	v_lshrrev_b32_e32 v1, 9, v7
	v_ashrrev_i32_e32 v18, 17, v7
	v_lshlrev_b32_e32 v13, 14, v17
	v_lshlrev_b32_sdwa v15, v10, v16 dst_sel:DWORD dst_unused:UNUSED_PAD src0_sel:DWORD src1_sel:BYTE_0
	v_lshlrev_b32_e32 v12, 14, v18
	v_lshlrev_b32_sdwa v14, v10, v1 dst_sel:DWORD dst_unused:UNUSED_PAD src0_sel:DWORD src1_sel:BYTE_0
	v_or_b32_e32 v13, v15, v13
	v_or_b32_e32 v12, v14, v12
	v_or_b32_e32 v14, v13, v2
	v_or_b32_e32 v12, v12, v3
	v_ashrrev_i32_e32 v15, 31, v14
	v_ashrrev_i32_e32 v13, 31, v12
	v_lshl_add_u64 v[14:15], v[14:15], 2, s[4:5]
	v_lshl_add_u64 v[12:13], v[12:13], 2, s[4:5]
	global_load_dword v19, v[14:15], off
	global_load_dword v20, v[12:13], off
	v_lshrrev_b32_e32 v12, 6, v7
	v_lshrrev_b32_e32 v13, 6, v6
	v_mul_i32_i24_e32 v14, 0x1100, v17
	v_and_b32_e32 v12, 7, v12
	v_and_b32_e32 v13, 7, v13
	v_mul_i32_i24_e32 v15, 0x1100, v18
	v_or_b32_sdwa v14, v14, v16 dst_sel:DWORD dst_unused:UNUSED_PAD src0_sel:DWORD src1_sel:BYTE_0
	v_or_b32_sdwa v1, v15, v1 dst_sel:DWORD dst_unused:UNUSED_PAD src0_sel:DWORD src1_sel:BYTE_0
	v_mad_u32_u24 v15, v12, s23, v5
	v_mad_u32_u24 v12, v13, s23, v4
	v_mul_lo_u32 v13, v14, s22
	v_add_u32_e32 v11, -2, v11
	v_mul_lo_u32 v1, v1, s22
	v_add3_u32 v12, v13, v12, s24
	v_cmp_eq_u32_e32 vcc, 0, v11
	v_add3_u32 v14, v1, v15, s24
	v_ashrrev_i32_e32 v13, 31, v12
	v_add_u32_e32 v7, s11, v7
	v_add_u32_e32 v6, s10, v6
	s_or_b64 s[20:21], vcc, s[20:21]
	v_ashrrev_i32_e32 v15, 31, v14
	v_lshl_add_u64 v[12:13], v[12:13], 1, s[18:19]
	v_lshl_add_u64 v[14:15], v[14:15], 1, s[18:19]
	s_waitcnt vmcnt(0)
	v_cvt_pk_bf16_f32 v1, v19, v20
	global_store_short v[12:13], v1, off sc1
	global_store_short_d16_hi v[14:15], v1, off sc1
	s_andn2_b64 exec, exec, s[20:21]
	s_cbranch_execnz .LBB0_532
	s_or_b64 exec, exec, s[20:21]
	v_cmp_ne_u32_e32 vcc, v8, v9
	v_mad_u64_u32 v[0:1], s[10:11], v9, s3, v[0:1]
	s_orn2_b64 s[20:21], vcc, exec

.LBB0_536:
	v_bfe_u32 v1, v0, 9, 8
	v_ashrrev_i32_e32 v3, 17, v0
	v_lshlrev_b32_e32 v5, 14, v3
	v_lshlrev_b32_e32 v6, 6, v1
	v_or3_b32 v6, v6, v5, v2
	v_ashrrev_i32_e32 v7, 31, v6
	v_lshl_add_u64 v[6:7], v[6:7], 2, s[4:5]
	global_load_dword v5, v[6:7], off
	v_mul_i32_i24_e32 v3, 0x1100, v3
	v_bfe_u32 v6, v0, 6, 3
	v_or_b32_e32 v1, v3, v1
	v_add_u32_e32 v0, s3, v0
	v_mad_u32_u24 v6, v6, s11, v4
	v_mul_lo_u32 v1, v1, s10
	v_cmp_lt_i32_e32 vcc, s21, v0
	v_add3_u32 v6, v1, v6, s20
	s_or_b64 s[0:1], vcc, s[0:1]
	v_ashrrev_i32_e32 v7, 31, v6
	v_lshl_add_u64 v[6:7], v[6:7], 1, s[18:19]
	s_waitcnt vmcnt(0)
	v_cvt_pk_bf16_f32 v1, v5, s0
	global_store_short v[6:7], v1, off sc1
	s_andn2_b64 exec, exec, s[0:1]
	s_cbranch_execnz .LBB0_536

.LBB0_538:
	s_cmp_gt_i32 s17, 3
	s_cselect_b64 s[4:5], -1, 0
	s_and_b64 s[0:1], s[6:7], s[4:5]
	s_andn2_b64 vcc, exec, s[0:1]
	s_cbranch_vccnz .LBB0_550
	s_waitcnt vmcnt(0)
	v_or_b32_e32 v0, v201, v200
	s_movk_i32 s0, 0x3ff
	v_and_or_b32 v0, v0, s0, v199
	v_cmp_eq_u32_e32 vcc, 0, v0
	s_waitcnt lgkmcnt(0)
	s_barrier
	s_and_saveexec_b64 s[0:1], vcc
	s_cbranch_execz .LBB0_549
	s_add_u32 s6, s14, 0x5be8c00
	s_addc_u32 s7, s15, 0
	s_lshl_b32 s3, s2, 1
	v_mov_b32_e32 v0, s3
	v_mov_b32_e32 v1, 0x9303
	global_store_short v0, v1, s[6:7] sc1
	s_cmp_lg_u32 s2, 0
	s_cbranch_scc1 .Lgbar_wait_2
	s_lshr_b32 s3, s33, 3
	s_bfm_b64 s[8:9], s3, 0
	s_cmpk_gt_u32 s33, 0x1ff
	s_cselect_b64 s[8:9], -1, s[8:9]
	s_mov_b64 exec, -1
	v_mbcnt_lo_u32_b32 v229, -1, 0
	v_mbcnt_hi_u32_b32 v229, -1, v229
	v_lshlrev_b32_e32 v229, 4, v229
	s_mov_b32 s10, 0x93039303
	s_mov_b64 exec, s[8:9]

.LBB0_554:
	v_lshl_add_u64 v[8:9], s[14:15], 0, v[2:3]
	v_add_co_u32_e32 v12, vcc, 0x607e000, v8
	s_nop 1
	v_addc_co_u32_e32 v13, vcc, 0, v9, vcc
	v_add_co_u32_e32 v8, vcc, 0x608e000, v8
	s_nop 1
	v_addc_co_u32_e32 v9, vcc, 0, v9, vcc
	global_load_dword v16, v[12:13], off
	global_load_dword v17, v[8:9], off offset:2048
	v_lshl_add_u64 v[8:9], s[14:15], 0, v[4:5]
	v_add_co_u32_e32 v12, vcc, 0x13e1f000, v8
	s_waitcnt vmcnt(0)
	v_add_f32_e32 v8, v16, v17
	v_addc_co_u32_e32 v13, vcc, 0, v9, vcc
	global_load_dwordx2 v[14:15], v[12:13], off
	v_fmamk_f32 v8, v8, 0x3b800000, v10
	v_rsq_f32_e32 v8, v8
	v_cmp_gt_i32_e32 vcc, s3, v11
	s_waitcnt vmcnt(0)
	v_lshlrev_b32_e32 v16, 16, v14
	v_and_b32_e32 v17, 0xffff0000, v14
	v_lshlrev_b32_e32 v14, 16, v15
	v_and_b32_e32 v15, 0xffff0000, v15
	v_pk_mul_f32 v[16:17], v[8:9], v[16:17] op_sel_hi:[0,1]
	v_pk_mul_f32 v[14:15], v[8:9], v[14:15] op_sel_hi:[0,1]
	v_cvt_pk_bf16_f32 v16, v16, v17
	v_cvt_pk_bf16_f32 v17, v14, v15
	global_store_dwordx2 v[12:13], v[16:17], off sc1
	s_and_saveexec_b64 s[24:25], vcc
	s_cbranch_execz .LBB0_553
	global_load_dwordx4 v[12:15], v[6:7], off
	v_mov_b32_e32 v9, v8
	s_waitcnt vmcnt(0)
	v_pk_mul_f32 v[12:13], v[8:9], v[12:13]
	v_pk_mul_f32 v[14:15], v[8:9], v[14:15]
	global_store_dwordx4 v[6:7], v[12:15], off sc1
	s_branch .LBB0_553

.LBB0_558:
	v_lshl_add_u64 v[6:7], s[14:15], 0, v[2:3]
	v_add_co_u32_e32 v10, vcc, 0x604e000, v6
	v_lshl_add_u64 v[8:9], s[14:15], 0, v[4:5]
	s_nop 0
	v_addc_co_u32_e32 v11, vcc, 0, v7, vcc
	v_add_co_u32_e32 v12, vcc, 0x605e000, v6
	global_load_dword v10, v[10:11], off
	s_nop 0
	v_addc_co_u32_e32 v13, vcc, 0, v7, vcc
	v_add_co_u32_e32 v6, vcc, 0x606e000, v6
	v_add_u32_e32 v0, s4, v0
	s_nop 0
	v_addc_co_u32_e32 v7, vcc, 0, v7, vcc
	global_load_dword v11, v[12:13], off
	global_load_dword v14, v[6:7], off
	v_add_co_u32_e32 v8, vcc, 0x1321f000, v8
	v_lshl_add_u64 v[2:3], v[2:3], 0, s[8:9]
	s_nop 0
	v_addc_co_u32_e32 v9, vcc, 0, v9, vcc
	global_load_dword v7, v[8:9], off
	global_load_dword v12, v[8:9], off offset:256
	global_load_dword v13, v[8:9], off offset:512
	v_cmp_lt_i32_e32 vcc, s3, v0
	v_lshl_add_u64 v[4:5], v[4:5], 0, s[18:19]
	s_or_b64 s[20:21], vcc, s[20:21]
	s_waitcnt vmcnt(4)
	v_add_f32_e32 v6, v10, v11
	s_waitcnt vmcnt(3)
	v_add_f32_e32 v6, v6, v14
	v_fmamk_f32 v14, v6, 0x3b2aaaab, v1
	v_rsq_f32_e32 v14, v14
	s_waitcnt vmcnt(2)
	v_lshlrev_b32_e32 v6, 16, v7
	v_and_b32_e32 v7, 0xffff0000, v7
	s_waitcnt vmcnt(1)
	v_lshlrev_b32_e32 v10, 16, v12
	v_and_b32_e32 v11, 0xffff0000, v12
	s_waitcnt vmcnt(0)
	v_lshlrev_b32_e32 v12, 16, v13
	v_and_b32_e32 v13, 0xffff0000, v13
	v_pk_mul_f32 v[6:7], v[14:15], v[6:7] op_sel_hi:[0,1]
	v_pk_mul_f32 v[10:11], v[14:15], v[10:11] op_sel_hi:[0,1]
	v_pk_mul_f32 v[12:13], v[14:15], v[12:13] op_sel_hi:[0,1]
	v_cvt_pk_bf16_f32 v6, v6, v7
	v_cvt_pk_bf16_f32 v7, v10, v11
	v_cvt_pk_bf16_f32 v10, v12, v13
	global_store_dword v[8:9], v6, off sc1
	global_store_dword v[8:9], v7, off offset:256 sc1
	global_store_dword v[8:9], v10, off offset:512 sc1
	s_andn2_b64 exec, exec, s[20:21]
	s_cbranch_execnz .LBB0_558

.LBB0_560:
	s_cmp_gt_i32 s17, 4
	s_cselect_b64 s[6:7], -1, 0
	s_and_b64 s[0:1], s[0:1], s[6:7]
	s_andn2_b64 vcc, exec, s[0:1]
	s_cbranch_vccnz .LBB0_572
	s_waitcnt vmcnt(0)
	v_or_b32_e32 v0, v201, v200
	s_movk_i32 s0, 0x3ff
	v_and_or_b32 v0, v0, s0, v199
	v_cmp_eq_u32_e32 vcc, 0, v0
	s_waitcnt lgkmcnt(0)
	s_barrier
	s_and_saveexec_b64 s[0:1], vcc
	s_cbranch_execz .LBB0_571
	s_add_u32 s4, s14, 0x5be8c00
	s_addc_u32 s5, s15, 0
	s_lshl_b32 s3, s2, 1
	v_mov_b32_e32 v0, s3
	v_mov_b32_e32 v1, 0x9304
	global_store_short v0, v1, s[4:5] sc1
	s_cmp_lg_u32 s2, 0
	s_cbranch_scc1 .Lgbar_wait_3
	s_lshr_b32 s3, s33, 3
	s_bfm_b64 s[8:9], s3, 0
	s_cmpk_gt_u32 s33, 0x1ff
	s_cselect_b64 s[8:9], -1, s[8:9]
	s_mov_b64 exec, -1
	v_mbcnt_lo_u32_b32 v229, -1, 0
	v_mbcnt_hi_u32_b32 v229, -1, v229
	v_lshlrev_b32_e32 v229, 4, v229
	s_mov_b32 s10, 0x93049304
	s_mov_b64 exec, s[8:9]

.LBB0_575:
	v_ashrrev_i32_e32 v73, 31, v72
	s_add_i32 s71, s71, s33
	v_cvt_pk_bf16_f32 v2, v70, s0
	v_lshl_add_u64 v[0:1], v[72:73], 1, s[6:7]
	s_cmpk_lt_i32 s71, 0x600
	global_store_short v[0:1], v2, off sc1
	s_cbranch_scc0 .LBB0_644

.LBB0_579:
	v_mov_b32_e32 v130, v49
	v_mov_b32_e32 v131, v33
	v_pk_mul_f32 v[130:131], v[130:131], v[130:131]
	s_mul_i32 s74, s72, 0x180
	v_add_f32_e32 v129, v130, v131
	ds_bpermute_b32 v130, v123, v129
	v_add_u32_e32 v131, s73, v80
	v_cndmask_b32_e64 v133, 0, 1, s[68:69]
	s_add_i32 s75, s74, 0xfffff400
	v_cvt_pk_bf16_f32 v135, v73, s0
	s_waitcnt lgkmcnt(0)
	v_add_f32_e32 v129, v129, v130
	ds_bpermute_b32 v130, v124, v129
	v_cvt_pk_bf16_f32 v136, v72, s0
	v_cmp_ne_u32_e64 s[0:1], 1, v133
	v_mov_b32_e32 v72, v33
	v_mov_b32_e32 v73, v49
	s_waitcnt lgkmcnt(0)
	v_add_f32_e32 v130, v129, v130
	ds_bpermute_b32 v132, v125, v130
	v_mul_lo_u32 v129, v131, s70
	v_add_u32_e32 v133, s75, v129
	v_add_u32_e32 v137, s76, v83
	s_andn2_b64 vcc, exec, s[68:69]
	s_waitcnt lgkmcnt(0)
	v_add_f32_e32 v131, v130, v132
	ds_bpermute_b32 v132, v127, v131
	v_add_u32_e32 v130, v133, v81
	s_waitcnt lgkmcnt(0)
	v_add_f32_e32 v134, v131, v132
	ds_bpermute_b32 v138, v126, v134
	v_add_u32_e32 v132, v133, v82
	v_ashrrev_i32_e32 v131, 31, v130
	v_ashrrev_i32_e32 v133, 31, v132
	v_lshl_add_u64 v[130:131], v[130:131], 1, s[6:7]
	s_waitcnt lgkmcnt(0)
	v_add_f32_e32 v134, v134, v138
	v_fmamk_f32 v134, v134, 0x3c800000, v119
	v_rsq_f32_e32 v134, v134
	v_lshl_add_u64 v[132:133], v[132:133], 1, s[6:7]
	global_store_short v[130:131], v135, off sc1
	global_store_short v[132:133], v136, off sc1
	v_pk_mul_f32 v[130:131], v[70:71], v[134:135] op_sel_hi:[1,0]
	s_nop 0
	v_pk_mul_f32 v[72:73], v[72:73], v[130:131]
	v_lshl_or_b32 v130, v137, 8, v142
	s_cbranch_vccnz .LBB0_581
	global_load_dwordx2 v[132:133], v130, s[8:9]
	s_waitcnt vmcnt(0)
	v_pk_mul_f32 v[136:137], v[72:73], v[132:133] op_sel_hi:[0,1]
	v_pk_mul_f32 v[134:135], v[72:73], v[132:133] op_sel:[1,1] op_sel_hi:[1,0]
	v_pk_fma_f32 v[72:73], v[72:73], v[132:133], v[136:137] op_sel:[1,1,0] op_sel_hi:[1,0,1] neg_lo:[0,0,1] neg_hi:[0,0,1]
	s_nop 0
	v_add_f32_e32 v72, v134, v136
.LBB0_581:
	v_mov_b32_e32 v132, v50
	v_mov_b32_e32 v133, v34
	v_pk_mul_f32 v[132:133], v[132:133], v[132:133]
	v_cvt_pk_bf16_f32 v138, v73, s0
	v_add_f32_e32 v131, v132, v133
	ds_bpermute_b32 v132, v123, v131
	v_add_u32_e32 v133, s73, v83
	v_mul_lo_u32 v133, v133, s70
	v_add_u32_e32 v135, s75, v133
	v_add_u32_e32 v134, v135, v81
	s_waitcnt lgkmcnt(0)
	v_add_f32_e32 v131, v131, v132
	ds_bpermute_b32 v132, v124, v131
	v_add_u32_e32 v136, v135, v82
	v_ashrrev_i32_e32 v135, 31, v134
	v_ashrrev_i32_e32 v137, 31, v136
	v_lshl_add_u64 v[134:135], v[134:135], 1, s[6:7]
	s_waitcnt lgkmcnt(0)
	v_add_f32_e32 v131, v131, v132
	ds_bpermute_b32 v132, v125, v131
	v_cvt_pk_bf16_f32 v139, v72, s0
	v_mov_b32_e32 v72, v34
	v_mov_b32_e32 v73, v50
	v_add_u32_e32 v140, s76, v84
	s_waitcnt lgkmcnt(0)
	v_add_f32_e32 v131, v131, v132
	ds_bpermute_b32 v132, v127, v131
	v_lshl_add_u64 v[136:137], v[136:137], 1, s[6:7]
	global_store_short v[134:135], v138, off sc1
	global_store_short v[136:137], v139, off sc1
	s_and_b64 vcc, exec, s[0:1]
	s_waitcnt lgkmcnt(0)
	v_add_f32_e32 v131, v131, v132
	ds_bpermute_b32 v132, v126, v131
	s_waitcnt lgkmcnt(0)
	v_add_f32_e32 v131, v131, v132
	v_fmamk_f32 v131, v131, 0x3c800000, v119
	v_rsq_f32_e32 v132, v131
	v_lshl_or_b32 v131, v140, 8, v142
	v_pk_mul_f32 v[134:135], v[70:71], v[132:133] op_sel_hi:[1,0]
	s_nop 0
	v_pk_mul_f32 v[72:73], v[72:73], v[134:135]
	s_cbranch_vccnz .LBB0_583
	global_load_dwordx2 v[134:135], v131, s[8:9]
	s_waitcnt vmcnt(0)
	v_pk_mul_f32 v[138:139], v[72:73], v[134:135] op_sel_hi:[0,1]
	v_pk_mul_f32 v[136:137], v[72:73], v[134:135] op_sel:[1,1] op_sel_hi:[1,0]
	v_pk_fma_f32 v[72:73], v[72:73], v[134:135], v[138:139] op_sel:[1,1,0] op_sel_hi:[1,0,1] neg_lo:[0,0,1] neg_hi:[0,0,1]
	s_nop 0
	v_add_f32_e32 v72, v136, v138
.LBB0_583:
	v_mov_b32_e32 v134, v51
	v_mov_b32_e32 v135, v35
	v_pk_mul_f32 v[134:135], v[134:135], v[134:135]
	v_cvt_pk_bf16_f32 v140, v73, s0
	v_add_f32_e32 v132, v134, v135
	ds_bpermute_b32 v134, v123, v132
	v_add_u32_e32 v135, s73, v84
	v_mul_lo_u32 v135, v135, s70
	v_add_u32_e32 v137, s75, v135
	v_add_u32_e32 v136, v137, v81
	s_waitcnt lgkmcnt(0)
	v_add_f32_e32 v132, v132, v134
	ds_bpermute_b32 v134, v124, v132
	v_add_u32_e32 v138, v137, v82
	v_ashrrev_i32_e32 v137, 31, v136
	v_ashrrev_i32_e32 v139, 31, v138
	v_lshl_add_u64 v[136:137], v[136:137], 1, s[6:7]
	s_waitcnt lgkmcnt(0)
	v_add_f32_e32 v132, v132, v134
	ds_bpermute_b32 v134, v125, v132
	v_cvt_pk_bf16_f32 v141, v72, s0
	v_mov_b32_e32 v72, v35
	v_mov_b32_e32 v73, v51
	v_add_u32_e32 v143, s76, v85
	s_waitcnt lgkmcnt(0)
	v_add_f32_e32 v132, v132, v134
	ds_bpermute_b32 v134, v127, v132
	v_lshl_add_u64 v[138:139], v[138:139], 1, s[6:7]
	global_store_short v[136:137], v140, off sc1
	global_store_short v[138:139], v141, off sc1
	s_and_b64 vcc, exec, s[0:1]
	s_waitcnt lgkmcnt(0)
	v_add_f32_e32 v132, v132, v134
	ds_bpermute_b32 v134, v126, v132
	s_waitcnt lgkmcnt(0)
	v_add_f32_e32 v132, v132, v134
	v_fmamk_f32 v132, v132, 0x3c800000, v119
	v_rsq_f32_e32 v132, v132
	s_nop 0
	v_pk_mul_f32 v[136:137], v[70:71], v[132:133] op_sel_hi:[1,0]
	s_nop 0
	v_pk_mul_f32 v[72:73], v[72:73], v[136:137]
	v_lshl_or_b32 v132, v143, 8, v142
	s_cbranch_vccnz .LBB0_585
	global_load_dwordx2 v[136:137], v132, s[8:9]
	s_waitcnt vmcnt(0)
	v_pk_mul_f32 v[140:141], v[72:73], v[136:137] op_sel_hi:[0,1]
	v_pk_mul_f32 v[138:139], v[72:73], v[136:137] op_sel:[1,1] op_sel_hi:[1,0]
	v_pk_fma_f32 v[72:73], v[72:73], v[136:137], v[140:141] op_sel:[1,1,0] op_sel_hi:[1,0,1] neg_lo:[0,0,1] neg_hi:[0,0,1]
	s_nop 0
	v_add_f32_e32 v72, v138, v140
.LBB0_585:
	v_mov_b32_e32 v136, v52
	v_mov_b32_e32 v137, v36
	v_pk_mul_f32 v[136:137], v[136:137], v[136:137]
	v_cvt_pk_bf16_f32 v143, v73, s0
	v_add_f32_e32 v134, v136, v137
	ds_bpermute_b32 v136, v123, v134
	v_add_u32_e32 v137, s73, v85
	v_mul_lo_u32 v137, v137, s70
	v_add_u32_e32 v139, s75, v137
	v_add_u32_e32 v138, v139, v81
	s_waitcnt lgkmcnt(0)
	v_add_f32_e32 v134, v134, v136
	ds_bpermute_b32 v136, v124, v134
	v_add_u32_e32 v140, v139, v82
	v_ashrrev_i32_e32 v139, 31, v138
	v_ashrrev_i32_e32 v141, 31, v140
	v_lshl_add_u64 v[138:139], v[138:139], 1, s[6:7]
	s_waitcnt lgkmcnt(0)
	v_add_f32_e32 v134, v134, v136
	ds_bpermute_b32 v136, v125, v134
	v_cvt_pk_bf16_f32 v144, v72, s0
	v_mov_b32_e32 v72, v36
	v_mov_b32_e32 v73, v52
	v_add_u32_e32 v145, s76, v86
	s_waitcnt lgkmcnt(0)
	v_add_f32_e32 v134, v134, v136
	ds_bpermute_b32 v136, v127, v134
	v_lshl_add_u64 v[140:141], v[140:141], 1, s[6:7]
	global_store_short v[138:139], v143, off sc1
	global_store_short v[140:141], v144, off sc1
	s_and_b64 vcc, exec, s[0:1]
	s_waitcnt lgkmcnt(0)
	v_add_f32_e32 v134, v134, v136
	ds_bpermute_b32 v136, v126, v134
	s_waitcnt lgkmcnt(0)
	v_add_f32_e32 v134, v134, v136
	v_fmamk_f32 v134, v134, 0x3c800000, v119
	v_rsq_f32_e32 v134, v134
	s_nop 0
	v_pk_mul_f32 v[138:139], v[70:71], v[134:135] op_sel_hi:[1,0]
	s_nop 0
	v_pk_mul_f32 v[72:73], v[72:73], v[138:139]
	v_lshl_or_b32 v134, v145, 8, v142
	s_cbranch_vccnz .LBB0_587
	global_load_dwordx2 v[138:139], v134, s[8:9]
	s_waitcnt vmcnt(0)
	v_pk_mul_f32 v[144:145], v[72:73], v[138:139] op_sel_hi:[0,1]
	v_pk_mul_f32 v[140:141], v[72:73], v[138:139] op_sel:[1,1] op_sel_hi:[1,0]
	v_pk_fma_f32 v[72:73], v[72:73], v[138:139], v[144:145] op_sel:[1,1,0] op_sel_hi:[1,0,1] neg_lo:[0,0,1] neg_hi:[0,0,1]
	s_nop 0
	v_add_f32_e32 v72, v140, v144
.LBB0_587:
	v_mov_b32_e32 v138, v53
	v_mov_b32_e32 v139, v37
	v_pk_mul_f32 v[138:139], v[138:139], v[138:139]
	v_cvt_pk_bf16_f32 v143, v73, s0
	v_add_f32_e32 v136, v138, v139
	ds_bpermute_b32 v138, v123, v136
	v_add_u32_e32 v139, s73, v86
	v_mul_lo_u32 v139, v139, s70
	v_add_u32_e32 v141, s75, v139
	v_add_u32_e32 v140, v141, v81
	s_waitcnt lgkmcnt(0)
	v_add_f32_e32 v136, v136, v138
	ds_bpermute_b32 v138, v124, v136
	v_add_u32_e32 v144, v141, v82
	v_ashrrev_i32_e32 v141, 31, v140
	v_ashrrev_i32_e32 v145, 31, v144
	v_lshl_add_u64 v[140:141], v[140:141], 1, s[6:7]
	s_waitcnt lgkmcnt(0)
	v_add_f32_e32 v136, v136, v138
	ds_bpermute_b32 v138, v125, v136
	v_cvt_pk_bf16_f32 v146, v72, s0
	v_mov_b32_e32 v72, v37
	v_mov_b32_e32 v73, v53
	v_add_u32_e32 v147, s76, v87
	s_waitcnt lgkmcnt(0)
	v_add_f32_e32 v136, v136, v138
	ds_bpermute_b32 v138, v127, v136
	v_lshl_add_u64 v[144:145], v[144:145], 1, s[6:7]
	global_store_short v[140:141], v143, off sc1
	global_store_short v[144:145], v146, off sc1
	s_and_b64 vcc, exec, s[0:1]
	s_waitcnt lgkmcnt(0)
	v_add_f32_e32 v136, v136, v138
	ds_bpermute_b32 v138, v126, v136
	s_waitcnt lgkmcnt(0)
	v_add_f32_e32 v136, v136, v138
	v_fmamk_f32 v136, v136, 0x3c800000, v119
	v_rsq_f32_e32 v136, v136
	s_nop 0
	v_pk_mul_f32 v[140:141], v[70:71], v[136:137] op_sel_hi:[1,0]
	s_nop 0
	v_pk_mul_f32 v[72:73], v[72:73], v[140:141]
	v_lshl_or_b32 v136, v147, 8, v142
	s_cbranch_vccnz .LBB0_589
	global_load_dwordx2 v[140:141], v136, s[8:9]
	s_waitcnt vmcnt(0)
	v_pk_mul_f32 v[146:147], v[72:73], v[140:141] op_sel_hi:[0,1]
	v_pk_mul_f32 v[144:145], v[72:73], v[140:141] op_sel:[1,1] op_sel_hi:[1,0]
	v_pk_fma_f32 v[72:73], v[72:73], v[140:141], v[146:147] op_sel:[1,1,0] op_sel_hi:[1,0,1] neg_lo:[0,0,1] neg_hi:[0,0,1]
	s_nop 0
	v_add_f32_e32 v72, v144, v146
.LBB0_589:
	v_mov_b32_e32 v140, v54
	v_mov_b32_e32 v141, v38
	v_pk_mul_f32 v[140:141], v[140:141], v[140:141]
	v_cvt_pk_bf16_f32 v143, v73, s0
	v_add_f32_e32 v138, v140, v141
	ds_bpermute_b32 v140, v123, v138
	v_add_u32_e32 v141, s73, v87
	v_mul_lo_u32 v141, v141, s70
	v_add_u32_e32 v145, s75, v141
	v_add_u32_e32 v144, v145, v81
	s_waitcnt lgkmcnt(0)
	v_add_f32_e32 v138, v138, v140
	ds_bpermute_b32 v140, v124, v138
	v_add_u32_e32 v146, v145, v82
	v_ashrrev_i32_e32 v145, 31, v144
	v_ashrrev_i32_e32 v147, 31, v146
	v_lshl_add_u64 v[144:145], v[144:145], 1, s[6:7]
	s_waitcnt lgkmcnt(0)
	v_add_f32_e32 v138, v138, v140
	ds_bpermute_b32 v140, v125, v138
	v_cvt_pk_bf16_f32 v148, v72, s0
	v_mov_b32_e32 v72, v38
	v_mov_b32_e32 v73, v54
	v_add_u32_e32 v149, s76, v88
	s_waitcnt lgkmcnt(0)
	v_add_f32_e32 v138, v138, v140
	ds_bpermute_b32 v140, v127, v138
	v_lshl_add_u64 v[146:147], v[146:147], 1, s[6:7]
	global_store_short v[144:145], v143, off sc1
	global_store_short v[146:147], v148, off sc1
	s_and_b64 vcc, exec, s[0:1]
	s_waitcnt lgkmcnt(0)
	v_add_f32_e32 v138, v138, v140
	ds_bpermute_b32 v140, v126, v138
	s_waitcnt lgkmcnt(0)
	v_add_f32_e32 v138, v138, v140
	v_fmamk_f32 v138, v138, 0x3c800000, v119
	v_rsq_f32_e32 v138, v138
	s_nop 0
	v_pk_mul_f32 v[144:145], v[70:71], v[138:139] op_sel_hi:[1,0]
	s_nop 0
	v_pk_mul_f32 v[72:73], v[72:73], v[144:145]
	v_lshl_or_b32 v138, v149, 8, v142
	s_cbranch_vccnz .LBB0_591
	global_load_dwordx2 v[144:145], v138, s[8:9]
	s_waitcnt vmcnt(0)
	v_pk_mul_f32 v[148:149], v[72:73], v[144:145] op_sel_hi:[0,1]
	v_pk_mul_f32 v[146:147], v[72:73], v[144:145] op_sel:[1,1] op_sel_hi:[1,0]
	v_pk_fma_f32 v[72:73], v[72:73], v[144:145], v[148:149] op_sel:[1,1,0] op_sel_hi:[1,0,1] neg_lo:[0,0,1] neg_hi:[0,0,1]
	s_nop 0
	v_add_f32_e32 v72, v146, v148
.LBB0_591:
	v_mov_b32_e32 v144, v55
	v_mov_b32_e32 v145, v39
	v_pk_mul_f32 v[144:145], v[144:145], v[144:145]
	v_cvt_pk_bf16_f32 v150, v72, s0
	v_add_f32_e32 v140, v144, v145
	ds_bpermute_b32 v143, v123, v140
	v_add_u32_e32 v144, s73, v88
	v_mul_lo_u32 v144, v144, s70
	v_add_u32_e32 v147, s75, v144
	v_add_u32_e32 v146, v147, v81
	s_waitcnt lgkmcnt(0)
	v_add_f32_e32 v140, v140, v143
	ds_bpermute_b32 v143, v124, v140
	v_add_u32_e32 v148, v147, v82
	v_ashrrev_i32_e32 v147, 31, v146
	v_cvt_pk_bf16_f32 v145, v73, s0
	v_ashrrev_i32_e32 v149, 31, v148
	s_waitcnt lgkmcnt(0)
	v_add_f32_e32 v140, v140, v143
	ds_bpermute_b32 v143, v125, v140
	v_lshl_add_u64 v[146:147], v[146:147], 1, s[6:7]
	v_mov_b32_e32 v72, v39
	v_mov_b32_e32 v73, v55
	v_add_u32_e32 v151, s76, v89
	s_waitcnt lgkmcnt(0)
	v_add_f32_e32 v140, v140, v143
	ds_bpermute_b32 v143, v127, v140
	v_lshl_add_u64 v[148:149], v[148:149], 1, s[6:7]
	global_store_short v[146:147], v145, off sc1
	global_store_short v[148:149], v150, off sc1
	s_and_b64 vcc, exec, s[0:1]
	s_waitcnt lgkmcnt(0)
	v_add_f32_e32 v140, v140, v143
	ds_bpermute_b32 v143, v126, v140
	s_waitcnt lgkmcnt(0)
	v_add_f32_e32 v140, v140, v143
	v_fmamk_f32 v140, v140, 0x3c800000, v119
	v_rsq_f32_e32 v140, v140
	s_nop 0
	v_pk_mul_f32 v[146:147], v[70:71], v[140:141] op_sel_hi:[1,0]
	s_nop 0
	v_pk_mul_f32 v[72:73], v[72:73], v[146:147]
	v_lshl_or_b32 v140, v151, 8, v142
	s_cbranch_vccnz .LBB0_593
	global_load_dwordx2 v[146:147], v140, s[8:9]
	s_waitcnt vmcnt(0)
	v_pk_mul_f32 v[150:151], v[72:73], v[146:147] op_sel_hi:[0,1]
	v_pk_mul_f32 v[148:149], v[72:73], v[146:147] op_sel:[1,1] op_sel_hi:[1,0]
	v_pk_fma_f32 v[72:73], v[72:73], v[146:147], v[150:151] op_sel:[1,1,0] op_sel_hi:[1,0,1] neg_lo:[0,0,1] neg_hi:[0,0,1]
	s_nop 0
	v_add_f32_e32 v72, v148, v150
.LBB0_593:
	v_mov_b32_e32 v146, v56
	v_mov_b32_e32 v147, v40
	v_pk_mul_f32 v[146:147], v[146:147], v[146:147]
	v_cvt_pk_bf16_f32 v153, v72, s0
	v_add_f32_e32 v143, v146, v147
	ds_bpermute_b32 v145, v123, v143
	v_add_u32_e32 v146, s73, v89
	v_mul_lo_u32 v146, v146, s70
	v_add_u32_e32 v149, s75, v146
	v_add_u32_e32 v148, v149, v81
	s_waitcnt lgkmcnt(0)
	v_add_f32_e32 v143, v143, v145
	ds_bpermute_b32 v145, v124, v143
	v_add_u32_e32 v150, v149, v82
	v_ashrrev_i32_e32 v149, 31, v148
	v_cvt_pk_bf16_f32 v147, v73, s0
	v_ashrrev_i32_e32 v151, 31, v150
	s_waitcnt lgkmcnt(0)
	v_add_f32_e32 v143, v143, v145
	ds_bpermute_b32 v145, v125, v143
	v_lshl_add_u64 v[148:149], v[148:149], 1, s[6:7]
	v_mov_b32_e32 v72, v40
	v_mov_b32_e32 v73, v56
	v_add_u32_e32 v154, s76, v90
	s_waitcnt lgkmcnt(0)
	v_add_f32_e32 v143, v143, v145
	ds_bpermute_b32 v145, v127, v143
	v_lshl_add_u64 v[150:151], v[150:151], 1, s[6:7]
	global_store_short v[148:149], v147, off sc1
	global_store_short v[150:151], v153, off sc1
	s_and_b64 vcc, exec, s[0:1]
	s_waitcnt lgkmcnt(0)
	v_add_f32_e32 v143, v143, v145
	ds_bpermute_b32 v145, v126, v143
	s_waitcnt lgkmcnt(0)
	v_add_f32_e32 v143, v143, v145
	v_fmamk_f32 v143, v143, 0x3c800000, v119
	v_rsq_f32_e32 v152, v143
	v_lshl_or_b32 v143, v154, 8, v142
	v_pk_mul_f32 v[148:149], v[70:71], v[152:153] op_sel_hi:[1,0]
	s_nop 0
	v_pk_mul_f32 v[72:73], v[72:73], v[148:149]
	s_cbranch_vccnz .LBB0_595
	global_load_dwordx2 v[148:149], v143, s[8:9]
	s_waitcnt vmcnt(0)
	v_pk_mul_f32 v[152:153], v[72:73], v[148:149] op_sel_hi:[0,1]
	v_pk_mul_f32 v[150:151], v[72:73], v[148:149] op_sel:[1,1] op_sel_hi:[1,0]
	v_pk_fma_f32 v[72:73], v[72:73], v[148:149], v[152:153] op_sel:[1,1,0] op_sel_hi:[1,0,1] neg_lo:[0,0,1] neg_hi:[0,0,1]
	s_nop 0
	v_add_f32_e32 v72, v150, v152
.LBB0_595:
	v_mov_b32_e32 v148, v57
	v_mov_b32_e32 v149, v41
	v_pk_mul_f32 v[148:149], v[148:149], v[148:149]
	v_cvt_pk_bf16_f32 v155, v72, s0
	v_add_f32_e32 v145, v148, v149
	ds_bpermute_b32 v147, v123, v145
	v_add_u32_e32 v148, s73, v90
	v_mul_lo_u32 v148, v148, s70
	v_add_u32_e32 v151, s75, v148
	v_add_u32_e32 v150, v151, v81
	s_waitcnt lgkmcnt(0)
	v_add_f32_e32 v145, v145, v147
	ds_bpermute_b32 v147, v124, v145
	v_add_u32_e32 v152, v151, v82
	v_ashrrev_i32_e32 v151, 31, v150
	v_cvt_pk_bf16_f32 v149, v73, s0
	v_ashrrev_i32_e32 v153, 31, v152
	s_waitcnt lgkmcnt(0)
	v_add_f32_e32 v145, v145, v147
	ds_bpermute_b32 v147, v125, v145
	v_lshl_add_u64 v[150:151], v[150:151], 1, s[6:7]
	v_mov_b32_e32 v72, v41
	v_mov_b32_e32 v73, v57
	v_add_u32_e32 v156, s76, v91
	s_waitcnt lgkmcnt(0)
	v_add_f32_e32 v145, v145, v147
	ds_bpermute_b32 v147, v127, v145
	v_lshl_add_u64 v[152:153], v[152:153], 1, s[6:7]
	global_store_short v[150:151], v149, off sc1
	global_store_short v[152:153], v155, off sc1
	s_and_b64 vcc, exec, s[0:1]
	s_waitcnt lgkmcnt(0)
	v_add_f32_e32 v145, v145, v147
	ds_bpermute_b32 v147, v126, v145
	s_waitcnt lgkmcnt(0)
	v_add_f32_e32 v145, v145, v147
	v_fmamk_f32 v145, v145, 0x3c800000, v119
	v_rsq_f32_e32 v154, v145
	v_lshl_or_b32 v145, v156, 8, v142
	v_pk_mul_f32 v[150:151], v[70:71], v[154:155] op_sel_hi:[1,0]
	s_nop 0
	v_pk_mul_f32 v[72:73], v[72:73], v[150:151]
	s_cbranch_vccnz .LBB0_597
	global_load_dwordx2 v[150:151], v145, s[8:9]
	s_waitcnt vmcnt(0)
	v_pk_mul_f32 v[154:155], v[72:73], v[150:151] op_sel_hi:[0,1]
	v_pk_mul_f32 v[152:153], v[72:73], v[150:151] op_sel:[1,1] op_sel_hi:[1,0]
	v_pk_fma_f32 v[72:73], v[72:73], v[150:151], v[154:155] op_sel:[1,1,0] op_sel_hi:[1,0,1] neg_lo:[0,0,1] neg_hi:[0,0,1]
	s_nop 0
	v_add_f32_e32 v72, v152, v154
.LBB0_597:
	v_mov_b32_e32 v150, v58
	v_mov_b32_e32 v151, v42
	v_pk_mul_f32 v[150:151], v[150:151], v[150:151]
	v_cvt_pk_bf16_f32 v157, v72, s0
	v_add_f32_e32 v147, v150, v151
	ds_bpermute_b32 v149, v123, v147
	v_add_u32_e32 v150, s73, v91
	v_mul_lo_u32 v150, v150, s70
	v_add_u32_e32 v153, s75, v150
	v_add_u32_e32 v152, v153, v81
	s_waitcnt lgkmcnt(0)
	v_add_f32_e32 v147, v147, v149
	ds_bpermute_b32 v149, v124, v147
	v_add_u32_e32 v154, v153, v82
	v_ashrrev_i32_e32 v153, 31, v152
	v_cvt_pk_bf16_f32 v151, v73, s0
	v_ashrrev_i32_e32 v155, 31, v154
	s_waitcnt lgkmcnt(0)
	v_add_f32_e32 v147, v147, v149
	ds_bpermute_b32 v149, v125, v147
	v_lshl_add_u64 v[152:153], v[152:153], 1, s[6:7]
	v_mov_b32_e32 v72, v42
	v_mov_b32_e32 v73, v58
	v_add_u32_e32 v158, s76, v92
	s_waitcnt lgkmcnt(0)
	v_add_f32_e32 v147, v147, v149
	ds_bpermute_b32 v149, v127, v147
	v_lshl_add_u64 v[154:155], v[154:155], 1, s[6:7]
	global_store_short v[152:153], v151, off sc1
	global_store_short v[154:155], v157, off sc1
	s_and_b64 vcc, exec, s[0:1]
	s_waitcnt lgkmcnt(0)
	v_add_f32_e32 v147, v147, v149
	ds_bpermute_b32 v149, v126, v147
	s_waitcnt lgkmcnt(0)
	v_add_f32_e32 v147, v147, v149
	v_fmamk_f32 v147, v147, 0x3c800000, v119
	v_rsq_f32_e32 v156, v147
	v_lshl_or_b32 v147, v158, 8, v142
	v_pk_mul_f32 v[152:153], v[70:71], v[156:157] op_sel_hi:[1,0]
	s_nop 0
	v_pk_mul_f32 v[72:73], v[72:73], v[152:153]
	s_cbranch_vccnz .LBB0_599
	global_load_dwordx2 v[152:153], v147, s[8:9]
	s_waitcnt vmcnt(0)
	v_pk_mul_f32 v[156:157], v[72:73], v[152:153] op_sel_hi:[0,1]
	v_pk_mul_f32 v[154:155], v[72:73], v[152:153] op_sel:[1,1] op_sel_hi:[1,0]
	v_pk_fma_f32 v[72:73], v[72:73], v[152:153], v[156:157] op_sel:[1,1,0] op_sel_hi:[1,0,1] neg_lo:[0,0,1] neg_hi:[0,0,1]
	s_nop 0
	v_add_f32_e32 v72, v154, v156
.LBB0_599:
	v_mov_b32_e32 v152, v59
	v_mov_b32_e32 v153, v43
	v_pk_mul_f32 v[152:153], v[152:153], v[152:153]
	v_cvt_pk_bf16_f32 v159, v72, s0
	v_add_f32_e32 v149, v152, v153
	ds_bpermute_b32 v151, v123, v149
	v_add_u32_e32 v152, s73, v92
	v_mul_lo_u32 v152, v152, s70
	v_add_u32_e32 v155, s75, v152
	v_add_u32_e32 v154, v155, v81
	s_waitcnt lgkmcnt(0)
	v_add_f32_e32 v149, v149, v151
	ds_bpermute_b32 v151, v124, v149
	v_add_u32_e32 v156, v155, v82
	v_ashrrev_i32_e32 v155, 31, v154
	v_cvt_pk_bf16_f32 v153, v73, s0
	v_ashrrev_i32_e32 v157, 31, v156
	s_waitcnt lgkmcnt(0)
	v_add_f32_e32 v149, v149, v151
	ds_bpermute_b32 v151, v125, v149
	v_lshl_add_u64 v[154:155], v[154:155], 1, s[6:7]
	v_mov_b32_e32 v72, v43
	v_mov_b32_e32 v73, v59
	v_add_u32_e32 v160, s76, v93
	s_waitcnt lgkmcnt(0)
	v_add_f32_e32 v149, v149, v151
	ds_bpermute_b32 v151, v127, v149
	v_lshl_add_u64 v[156:157], v[156:157], 1, s[6:7]
	global_store_short v[154:155], v153, off sc1
	global_store_short v[156:157], v159, off sc1
	s_and_b64 vcc, exec, s[0:1]
	s_waitcnt lgkmcnt(0)
	v_add_f32_e32 v149, v149, v151
	ds_bpermute_b32 v151, v126, v149
	s_waitcnt lgkmcnt(0)
	v_add_f32_e32 v149, v149, v151
	v_fmamk_f32 v149, v149, 0x3c800000, v119
	v_rsq_f32_e32 v158, v149
	v_lshl_or_b32 v149, v160, 8, v142
	v_pk_mul_f32 v[154:155], v[70:71], v[158:159] op_sel_hi:[1,0]
	s_nop 0
	v_pk_mul_f32 v[72:73], v[72:73], v[154:155]
	s_cbranch_vccnz .LBB0_601
	global_load_dwordx2 v[154:155], v149, s[8:9]
	s_waitcnt vmcnt(0)
	v_pk_mul_f32 v[158:159], v[72:73], v[154:155] op_sel_hi:[0,1]
	v_pk_mul_f32 v[156:157], v[72:73], v[154:155] op_sel:[1,1] op_sel_hi:[1,0]
	v_pk_fma_f32 v[72:73], v[72:73], v[154:155], v[158:159] op_sel:[1,1,0] op_sel_hi:[1,0,1] neg_lo:[0,0,1] neg_hi:[0,0,1]
	s_nop 0
	v_add_f32_e32 v72, v156, v158
.LBB0_601:
	v_mov_b32_e32 v154, v60
	v_mov_b32_e32 v155, v44
	v_pk_mul_f32 v[154:155], v[154:155], v[154:155]
	v_cvt_pk_bf16_f32 v161, v72, s0
	v_add_f32_e32 v151, v154, v155
	ds_bpermute_b32 v153, v123, v151
	v_add_u32_e32 v154, s73, v93
	v_mul_lo_u32 v154, v154, s70
	v_add_u32_e32 v157, s75, v154
	v_add_u32_e32 v156, v157, v81
	s_waitcnt lgkmcnt(0)
	v_add_f32_e32 v151, v151, v153
	ds_bpermute_b32 v153, v124, v151
	v_add_u32_e32 v158, v157, v82
	v_ashrrev_i32_e32 v157, 31, v156
	v_cvt_pk_bf16_f32 v155, v73, s0
	v_ashrrev_i32_e32 v159, 31, v158
	s_waitcnt lgkmcnt(0)
	v_add_f32_e32 v151, v151, v153
	ds_bpermute_b32 v153, v125, v151
	v_lshl_add_u64 v[156:157], v[156:157], 1, s[6:7]
	v_mov_b32_e32 v72, v44
	v_mov_b32_e32 v73, v60
	v_add_u32_e32 v162, s76, v94
	s_waitcnt lgkmcnt(0)
	v_add_f32_e32 v151, v151, v153
	ds_bpermute_b32 v153, v127, v151
	v_lshl_add_u64 v[158:159], v[158:159], 1, s[6:7]
	global_store_short v[156:157], v155, off sc1
	global_store_short v[158:159], v161, off sc1
	s_and_b64 vcc, exec, s[0:1]
	s_waitcnt lgkmcnt(0)
	v_add_f32_e32 v151, v151, v153
	ds_bpermute_b32 v153, v126, v151
	s_waitcnt lgkmcnt(0)
	v_add_f32_e32 v151, v151, v153
	v_fmamk_f32 v151, v151, 0x3c800000, v119
	v_rsq_f32_e32 v160, v151
	v_lshl_or_b32 v151, v162, 8, v142
	v_pk_mul_f32 v[156:157], v[70:71], v[160:161] op_sel_hi:[1,0]
	s_nop 0
	v_pk_mul_f32 v[72:73], v[72:73], v[156:157]
	s_cbranch_vccnz .LBB0_603
	global_load_dwordx2 v[156:157], v151, s[8:9]
	s_waitcnt vmcnt(0)
	v_pk_mul_f32 v[160:161], v[72:73], v[156:157] op_sel_hi:[0,1]
	v_pk_mul_f32 v[158:159], v[72:73], v[156:157] op_sel:[1,1] op_sel_hi:[1,0]
	v_pk_fma_f32 v[72:73], v[72:73], v[156:157], v[160:161] op_sel:[1,1,0] op_sel_hi:[1,0,1] neg_lo:[0,0,1] neg_hi:[0,0,1]
	s_nop 0
	v_add_f32_e32 v72, v158, v160
.LBB0_603:
	v_mov_b32_e32 v156, v61
	v_mov_b32_e32 v157, v45
	v_pk_mul_f32 v[156:157], v[156:157], v[156:157]
	v_cvt_pk_bf16_f32 v163, v72, s0
	v_add_f32_e32 v153, v156, v157
	ds_bpermute_b32 v155, v123, v153
	v_add_u32_e32 v156, s73, v94
	v_mul_lo_u32 v156, v156, s70
	v_add_u32_e32 v159, s75, v156
	v_add_u32_e32 v158, v159, v81
	s_waitcnt lgkmcnt(0)
	v_add_f32_e32 v153, v153, v155
	ds_bpermute_b32 v155, v124, v153
	v_add_u32_e32 v160, v159, v82
	v_ashrrev_i32_e32 v159, 31, v158
	v_cvt_pk_bf16_f32 v157, v73, s0
	v_ashrrev_i32_e32 v161, 31, v160
	s_waitcnt lgkmcnt(0)
	v_add_f32_e32 v153, v153, v155
	ds_bpermute_b32 v155, v125, v153
	v_lshl_add_u64 v[158:159], v[158:159], 1, s[6:7]
	v_mov_b32_e32 v72, v45
	v_mov_b32_e32 v73, v61
	v_add_u32_e32 v164, s76, v95
	s_waitcnt lgkmcnt(0)
	v_add_f32_e32 v153, v153, v155
	ds_bpermute_b32 v155, v127, v153
	v_lshl_add_u64 v[160:161], v[160:161], 1, s[6:7]
	global_store_short v[158:159], v157, off sc1
	global_store_short v[160:161], v163, off sc1
	s_and_b64 vcc, exec, s[0:1]
	s_waitcnt lgkmcnt(0)
	v_add_f32_e32 v153, v153, v155
	ds_bpermute_b32 v155, v126, v153
	s_waitcnt lgkmcnt(0)
	v_add_f32_e32 v153, v153, v155
	v_fmamk_f32 v153, v153, 0x3c800000, v119
	v_rsq_f32_e32 v162, v153
	v_lshl_or_b32 v153, v164, 8, v142
	v_pk_mul_f32 v[158:159], v[70:71], v[162:163] op_sel_hi:[1,0]
	s_nop 0
	v_pk_mul_f32 v[72:73], v[72:73], v[158:159]
	s_cbranch_vccnz .LBB0_605
	global_load_dwordx2 v[158:159], v153, s[8:9]
	s_waitcnt vmcnt(0)
	v_pk_mul_f32 v[162:163], v[72:73], v[158:159] op_sel_hi:[0,1]
	v_pk_mul_f32 v[160:161], v[72:73], v[158:159] op_sel:[1,1] op_sel_hi:[1,0]
	v_pk_fma_f32 v[72:73], v[72:73], v[158:159], v[162:163] op_sel:[1,1,0] op_sel_hi:[1,0,1] neg_lo:[0,0,1] neg_hi:[0,0,1]
	s_nop 0
	v_add_f32_e32 v72, v160, v162
.LBB0_605:
	v_mov_b32_e32 v158, v62
	v_mov_b32_e32 v159, v46
	v_pk_mul_f32 v[158:159], v[158:159], v[158:159]
	v_cvt_pk_bf16_f32 v163, v73, s0
	v_add_f32_e32 v155, v158, v159
	ds_bpermute_b32 v157, v123, v155
	v_add_u32_e32 v158, s73, v95
	v_cvt_pk_bf16_f32 v164, v72, s0
	v_mov_b32_e32 v72, v46
	v_mov_b32_e32 v73, v62
	s_waitcnt lgkmcnt(0)
	v_add_f32_e32 v155, v155, v157
	ds_bpermute_b32 v157, v124, v155
	v_add_u32_e32 v165, s76, v96
	s_and_b64 vcc, exec, s[0:1]
	s_waitcnt lgkmcnt(0)
	v_add_f32_e32 v155, v155, v157
	ds_bpermute_b32 v157, v125, v155
	s_waitcnt lgkmcnt(0)
	v_add_f32_e32 v155, v155, v157
	ds_bpermute_b32 v159, v127, v155
	v_mul_lo_u32 v157, v158, s70
	v_add_u32_e32 v160, s75, v157
	v_add_u32_e32 v158, v160, v81
	v_add_u32_e32 v160, v160, v82
	s_waitcnt lgkmcnt(0)
	v_add_f32_e32 v155, v155, v159
	ds_bpermute_b32 v162, v126, v155
	v_ashrrev_i32_e32 v159, 31, v158
	v_ashrrev_i32_e32 v161, 31, v160
	v_lshl_add_u64 v[158:159], v[158:159], 1, s[6:7]
	v_lshl_add_u64 v[160:161], v[160:161], 1, s[6:7]
	s_waitcnt lgkmcnt(0)
	v_add_f32_e32 v155, v155, v162
	v_fmamk_f32 v155, v155, 0x3c800000, v119
	v_rsq_f32_e32 v162, v155
	global_store_short v[158:159], v163, off sc1
	global_store_short v[160:161], v164, off sc1
	v_lshl_or_b32 v155, v165, 8, v142
	v_pk_mul_f32 v[158:159], v[70:71], v[162:163] op_sel_hi:[1,0]
	s_nop 0
	v_pk_mul_f32 v[72:73], v[72:73], v[158:159]
	s_cbranch_vccnz .LBB0_607
	global_load_dwordx2 v[158:159], v155, s[8:9]
	s_waitcnt vmcnt(0)
	v_pk_mul_f32 v[162:163], v[72:73], v[158:159] op_sel_hi:[0,1]
	v_pk_mul_f32 v[160:161], v[72:73], v[158:159] op_sel:[1,1] op_sel_hi:[1,0]
	v_pk_fma_f32 v[72:73], v[72:73], v[158:159], v[162:163] op_sel:[1,1,0] op_sel_hi:[1,0,1] neg_lo:[0,0,1] neg_hi:[0,0,1]
	s_nop 0
	v_add_f32_e32 v72, v160, v162
.LBB0_607:
	v_mov_b32_e32 v158, v63
	v_mov_b32_e32 v159, v47
	v_pk_mul_f32 v[158:159], v[158:159], v[158:159]
	v_add_u32_e32 v160, s73, v96
	v_add_f32_e32 v158, v158, v159
	ds_bpermute_b32 v159, v123, v158
	v_cvt_pk_bf16_f32 v165, v73, s0
	v_cvt_pk_bf16_f32 v166, v72, s0
	v_mov_b32_e32 v72, v47
	v_mov_b32_e32 v73, v63
	s_waitcnt lgkmcnt(0)
	v_add_f32_e32 v158, v158, v159
	ds_bpermute_b32 v159, v124, v158
	v_add_u32_e32 v167, s76, v97
	s_and_b64 vcc, exec, s[0:1]
	v_lshl_or_b32 v142, v167, 8, v142
	s_waitcnt lgkmcnt(0)
	v_add_f32_e32 v158, v158, v159
	ds_bpermute_b32 v159, v125, v158
	s_waitcnt lgkmcnt(0)
	v_add_f32_e32 v159, v158, v159
	ds_bpermute_b32 v161, v127, v159
	v_mul_lo_u32 v158, v160, s70
	v_add_u32_e32 v162, s75, v158
	v_add_u32_e32 v160, v162, v81
	v_add_u32_e32 v162, v162, v82
	s_waitcnt lgkmcnt(0)
	v_add_f32_e32 v159, v159, v161
	ds_bpermute_b32 v164, v126, v159
	v_ashrrev_i32_e32 v161, 31, v160
	v_ashrrev_i32_e32 v163, 31, v162
	v_lshl_add_u64 v[160:161], v[160:161], 1, s[6:7]
	v_lshl_add_u64 v[162:163], v[162:163], 1, s[6:7]
	s_waitcnt lgkmcnt(0)
	v_add_f32_e32 v159, v159, v164
	v_fmamk_f32 v159, v159, 0x3c800000, v119
	v_rsq_f32_e32 v164, v159
	global_store_short v[160:161], v165, off sc1
	global_store_short v[162:163], v166, off sc1
	v_pk_mul_f32 v[160:161], v[70:71], v[164:165] op_sel_hi:[1,0]
	s_nop 0
	v_pk_mul_f32 v[72:73], v[72:73], v[160:161]
	s_cbranch_vccnz .LBB0_609
	global_load_dwordx2 v[160:161], v142, s[8:9]
	s_waitcnt vmcnt(0)
	v_pk_mul_f32 v[164:165], v[72:73], v[160:161] op_sel_hi:[0,1]
	v_pk_mul_f32 v[162:163], v[72:73], v[160:161] op_sel:[1,1] op_sel_hi:[1,0]
	v_pk_fma_f32 v[72:73], v[72:73], v[160:161], v[164:165] op_sel:[1,1,0] op_sel_hi:[1,0,1] neg_lo:[0,0,1] neg_hi:[0,0,1]
	s_nop 0
	v_add_f32_e32 v72, v162, v164
.LBB0_609:
	v_mov_b32_e32 v160, v16
	v_mov_b32_e32 v161, v0
	v_pk_mul_f32 v[160:161], v[160:161], v[160:161]
	v_cvt_pk_bf16_f32 v165, v73, s0
	v_add_f32_e32 v159, v160, v161
	ds_bpermute_b32 v160, v123, v159
	v_add_u32_e32 v161, s73, v97
	v_cvt_pk_bf16_f32 v166, v72, s0
	v_mov_b32_e32 v72, v0
	v_mov_b32_e32 v73, v16
	s_waitcnt lgkmcnt(0)
	v_add_f32_e32 v159, v159, v160
	ds_bpermute_b32 v160, v124, v159
	s_and_b64 vcc, exec, s[0:1]
	s_waitcnt lgkmcnt(0)
	v_add_f32_e32 v159, v159, v160
	ds_bpermute_b32 v160, v125, v159
	s_waitcnt lgkmcnt(0)
	v_add_f32_e32 v162, v159, v160
	ds_bpermute_b32 v163, v127, v162
	v_mul_lo_u32 v159, v161, s70
	v_add_u32_e32 v161, s75, v159
	v_add_u32_e32 v160, v161, v81
	s_waitcnt lgkmcnt(0)
	v_add_f32_e32 v164, v162, v163
	ds_bpermute_b32 v167, v126, v164
	v_add_u32_e32 v162, v161, v82
	v_ashrrev_i32_e32 v161, 31, v160
	v_ashrrev_i32_e32 v163, 31, v162
	v_lshl_add_u64 v[160:161], v[160:161], 1, s[6:7]
	s_waitcnt lgkmcnt(0)
	v_add_f32_e32 v164, v164, v167
	v_fmamk_f32 v164, v164, 0x3c800000, v119
	v_rsq_f32_e32 v164, v164
	v_lshl_add_u64 v[162:163], v[162:163], 1, s[6:7]
	global_store_short v[160:161], v165, off sc1
	global_store_short v[162:163], v166, off sc1
	v_pk_mul_f32 v[160:161], v[70:71], v[164:165] op_sel_hi:[1,0]
	s_nop 0
	v_pk_mul_f32 v[72:73], v[72:73], v[160:161]
	s_cbranch_vccnz .LBB0_611
	global_load_dwordx2 v[160:161], v128, s[8:9]
	s_waitcnt vmcnt(0)
	v_pk_mul_f32 v[164:165], v[72:73], v[160:161] op_sel_hi:[0,1]
	v_pk_mul_f32 v[162:163], v[72:73], v[160:161] op_sel:[1,1] op_sel_hi:[1,0]
	v_pk_fma_f32 v[72:73], v[72:73], v[160:161], v[164:165] op_sel:[1,1,0] op_sel_hi:[1,0,1] neg_lo:[0,0,1] neg_hi:[0,0,1]
	s_nop 0
	v_add_f32_e32 v72, v162, v164
.LBB0_611:
	v_mov_b32_e32 v160, v17
	v_mov_b32_e32 v161, v1
	v_pk_mul_f32 v[160:161], v[160:161], v[160:161]
	s_addk_i32 s74, 0xf4c0
	v_add_f32_e32 v128, v160, v161
	ds_bpermute_b32 v160, v123, v128
	v_add_u32_e32 v129, s74, v129
	v_cvt_pk_bf16_f32 v163, v73, s0
	v_cvt_pk_bf16_f32 v164, v72, s0
	v_mov_b32_e32 v72, v1
	s_waitcnt lgkmcnt(0)
	v_add_f32_e32 v128, v128, v160
	ds_bpermute_b32 v160, v124, v128
	v_mov_b32_e32 v73, v17
	s_and_b64 vcc, exec, s[0:1]
	s_waitcnt lgkmcnt(0)
	v_add_f32_e32 v128, v128, v160
	ds_bpermute_b32 v160, v125, v128
	s_waitcnt lgkmcnt(0)
	v_add_f32_e32 v160, v128, v160
	ds_bpermute_b32 v161, v127, v160
	v_add_u32_e32 v128, v129, v81
	s_waitcnt lgkmcnt(0)
	v_add_f32_e32 v162, v160, v161
	ds_bpermute_b32 v165, v126, v162
	v_add_u32_e32 v160, v129, v82
	v_ashrrev_i32_e32 v129, 31, v128
	v_ashrrev_i32_e32 v161, 31, v160
	v_lshl_add_u64 v[128:129], v[128:129], 1, s[6:7]
	s_waitcnt lgkmcnt(0)
	v_add_f32_e32 v162, v162, v165
	v_fmamk_f32 v162, v162, 0x3c800000, v119
	v_rsq_f32_e32 v162, v162
	v_lshl_add_u64 v[160:161], v[160:161], 1, s[6:7]
	global_store_short v[128:129], v163, off sc1
	global_store_short v[160:161], v164, off sc1
	v_pk_mul_f32 v[128:129], v[70:71], v[162:163] op_sel_hi:[1,0]
	s_nop 0
	v_pk_mul_f32 v[72:73], v[72:73], v[128:129]
	s_cbranch_vccnz .LBB0_613
	global_load_dwordx2 v[128:129], v130, s[8:9]
	s_waitcnt vmcnt(0)
	v_pk_mul_f32 v[162:163], v[72:73], v[128:129] op_sel_hi:[0,1]
	v_pk_mul_f32 v[160:161], v[72:73], v[128:129] op_sel:[1,1] op_sel_hi:[1,0]
	v_pk_fma_f32 v[72:73], v[72:73], v[128:129], v[162:163] op_sel:[1,1,0] op_sel_hi:[1,0,1] neg_lo:[0,0,1] neg_hi:[0,0,1]
	s_nop 0
	v_add_f32_e32 v72, v160, v162
.LBB0_613:
	v_mov_b32_e32 v128, v18
	v_mov_b32_e32 v129, v2
	v_pk_mul_f32 v[128:129], v[128:129], v[128:129]
	v_add_u32_e32 v130, s74, v133
	v_add_f32_e32 v128, v128, v129
	ds_bpermute_b32 v129, v123, v128
	v_add_u32_e32 v160, v130, v82
	v_cvt_pk_bf16_f32 v162, v73, s0
	v_ashrrev_i32_e32 v161, 31, v160
	v_cvt_pk_bf16_f32 v163, v72, s0
	s_waitcnt lgkmcnt(0)
	v_add_f32_e32 v128, v128, v129
	ds_bpermute_b32 v129, v124, v128
	v_mov_b32_e32 v72, v2
	v_mov_b32_e32 v73, v18
	v_lshl_add_u64 v[160:161], v[160:161], 1, s[6:7]
	s_and_b64 vcc, exec, s[0:1]
	s_waitcnt lgkmcnt(0)
	v_add_f32_e32 v128, v128, v129
	ds_bpermute_b32 v129, v125, v128
	s_waitcnt lgkmcnt(0)
	v_add_f32_e32 v129, v128, v129
	ds_bpermute_b32 v133, v127, v129
	v_add_u32_e32 v128, v130, v81
	s_waitcnt lgkmcnt(0)
	v_add_f32_e32 v133, v129, v133
	ds_bpermute_b32 v164, v126, v133
	v_ashrrev_i32_e32 v129, 31, v128
	v_lshl_add_u64 v[128:129], v[128:129], 1, s[6:7]
	global_store_short v[128:129], v162, off sc1
	global_store_short v[160:161], v163, off sc1
	s_waitcnt lgkmcnt(0)
	v_add_f32_e32 v130, v133, v164
	v_fmamk_f32 v130, v130, 0x3c800000, v119
	v_rsq_f32_e32 v130, v130
	s_nop 0
	v_pk_mul_f32 v[128:129], v[70:71], v[130:131] op_sel_hi:[1,0]
	s_nop 0
	v_pk_mul_f32 v[72:73], v[72:73], v[128:129]
	s_cbranch_vccnz .LBB0_615
	global_load_dwordx2 v[128:129], v131, s[8:9]
	s_waitcnt vmcnt(0)
	v_pk_mul_f32 v[160:161], v[72:73], v[128:129] op_sel_hi:[0,1]
	v_pk_mul_f32 v[130:131], v[72:73], v[128:129] op_sel:[1,1] op_sel_hi:[1,0]
	v_pk_fma_f32 v[72:73], v[72:73], v[128:129], v[160:161] op_sel:[1,1,0] op_sel_hi:[1,0,1] neg_lo:[0,0,1] neg_hi:[0,0,1]
	s_nop 0
	v_add_f32_e32 v72, v130, v160
.LBB0_615:
	v_mov_b32_e32 v128, v19
	v_mov_b32_e32 v129, v3
	v_pk_mul_f32 v[128:129], v[128:129], v[128:129]
	v_add_u32_e32 v130, s74, v135
	v_add_f32_e32 v128, v128, v129
	ds_bpermute_b32 v129, v123, v128
	v_cvt_pk_bf16_f32 v133, v73, s0
	v_cvt_pk_bf16_f32 v135, v72, s0
	v_mov_b32_e32 v72, v3
	v_mov_b32_e32 v73, v19
	s_waitcnt lgkmcnt(0)
	v_add_f32_e32 v128, v128, v129
	ds_bpermute_b32 v129, v124, v128
	s_and_b64 vcc, exec, s[0:1]
	s_waitcnt lgkmcnt(0)
	v_add_f32_e32 v128, v128, v129
	ds_bpermute_b32 v129, v125, v128
	s_waitcnt lgkmcnt(0)
	v_add_f32_e32 v129, v128, v129
	ds_bpermute_b32 v131, v127, v129
	v_add_u32_e32 v128, v130, v81
	v_add_u32_e32 v130, v130, v82
	s_waitcnt lgkmcnt(0)
	v_add_f32_e32 v160, v129, v131
	ds_bpermute_b32 v161, v126, v160
	v_ashrrev_i32_e32 v129, 31, v128
	v_ashrrev_i32_e32 v131, 31, v130
	v_lshl_add_u64 v[128:129], v[128:129], 1, s[6:7]
	v_lshl_add_u64 v[130:131], v[130:131], 1, s[6:7]
	s_waitcnt lgkmcnt(0)
	v_add_f32_e32 v160, v160, v161
	v_fmamk_f32 v160, v160, 0x3c800000, v119
	v_rsq_f32_e32 v160, v160
	global_store_short v[128:129], v133, off sc1
	global_store_short v[130:131], v135, off sc1
	v_pk_mul_f32 v[128:129], v[70:71], v[160:161] op_sel_hi:[1,0]
	s_nop 0
	v_pk_mul_f32 v[72:73], v[72:73], v[128:129]
	s_cbranch_vccnz .LBB0_617
	global_load_dwordx2 v[128:129], v132, s[8:9]
	s_waitcnt vmcnt(0)
	v_pk_mul_f32 v[132:133], v[72:73], v[128:129] op_sel_hi:[0,1]
	v_pk_mul_f32 v[130:131], v[72:73], v[128:129] op_sel:[1,1] op_sel_hi:[1,0]
	v_pk_fma_f32 v[72:73], v[72:73], v[128:129], v[132:133] op_sel:[1,1,0] op_sel_hi:[1,0,1] neg_lo:[0,0,1] neg_hi:[0,0,1]
	s_nop 0
	v_add_f32_e32 v72, v130, v132
.LBB0_617:
	v_mov_b32_e32 v128, v20
	v_mov_b32_e32 v129, v4
	v_pk_mul_f32 v[128:129], v[128:129], v[128:129]
	v_add_u32_e32 v130, s74, v137
	v_add_f32_e32 v128, v128, v129
	ds_bpermute_b32 v129, v123, v128
	v_cvt_pk_bf16_f32 v133, v73, s0
	v_cvt_pk_bf16_f32 v135, v72, s0
	v_mov_b32_e32 v72, v4
	v_mov_b32_e32 v73, v20
	s_waitcnt lgkmcnt(0)
	v_add_f32_e32 v128, v128, v129
	ds_bpermute_b32 v129, v124, v128
	s_and_b64 vcc, exec, s[0:1]
	s_waitcnt lgkmcnt(0)
	v_add_f32_e32 v128, v128, v129
	ds_bpermute_b32 v129, v125, v128
	s_waitcnt lgkmcnt(0)
	v_add_f32_e32 v129, v128, v129
	ds_bpermute_b32 v131, v127, v129
	v_add_u32_e32 v128, v130, v81
	v_add_u32_e32 v130, v130, v82
	s_waitcnt lgkmcnt(0)
	v_add_f32_e32 v132, v129, v131
	ds_bpermute_b32 v137, v126, v132
	v_ashrrev_i32_e32 v129, 31, v128
	v_ashrrev_i32_e32 v131, 31, v130
	v_lshl_add_u64 v[128:129], v[128:129], 1, s[6:7]
	v_lshl_add_u64 v[130:131], v[130:131], 1, s[6:7]
	s_waitcnt lgkmcnt(0)
	v_add_f32_e32 v132, v132, v137
	v_fmamk_f32 v132, v132, 0x3c800000, v119
	v_rsq_f32_e32 v132, v132
	global_store_short v[128:129], v133, off sc1
	global_store_short v[130:131], v135, off sc1
	v_pk_mul_f32 v[128:129], v[70:71], v[132:133] op_sel_hi:[1,0]
	s_nop 0
	v_pk_mul_f32 v[72:73], v[72:73], v[128:129]
	s_cbranch_vccnz .LBB0_619
	global_load_dwordx2 v[128:129], v134, s[8:9]
	s_waitcnt vmcnt(0)
	v_pk_mul_f32 v[132:133], v[72:73], v[128:129] op_sel_hi:[0,1]
	v_pk_mul_f32 v[130:131], v[72:73], v[128:129] op_sel:[1,1] op_sel_hi:[1,0]
	v_pk_fma_f32 v[72:73], v[72:73], v[128:129], v[132:133] op_sel:[1,1,0] op_sel_hi:[1,0,1] neg_lo:[0,0,1] neg_hi:[0,0,1]
	s_nop 0
	v_add_f32_e32 v72, v130, v132
.LBB0_619:
	v_mov_b32_e32 v128, v21
	v_mov_b32_e32 v129, v5
	v_pk_mul_f32 v[128:129], v[128:129], v[128:129]
	v_add_u32_e32 v130, s74, v139
	v_add_f32_e32 v128, v128, v129
	ds_bpermute_b32 v129, v123, v128
	v_cvt_pk_bf16_f32 v133, v73, s0
	v_cvt_pk_bf16_f32 v134, v72, s0
	v_mov_b32_e32 v72, v5
	v_mov_b32_e32 v73, v21
	s_waitcnt lgkmcnt(0)
	v_add_f32_e32 v128, v128, v129
	ds_bpermute_b32 v129, v124, v128
	s_and_b64 vcc, exec, s[0:1]
	s_waitcnt lgkmcnt(0)
	v_add_f32_e32 v128, v128, v129
	ds_bpermute_b32 v129, v125, v128
	s_waitcnt lgkmcnt(0)
	v_add_f32_e32 v129, v128, v129
	ds_bpermute_b32 v131, v127, v129
	v_add_u32_e32 v128, v130, v81
	v_add_u32_e32 v130, v130, v82
	s_waitcnt lgkmcnt(0)
	v_add_f32_e32 v132, v129, v131
	ds_bpermute_b32 v135, v126, v132
	v_ashrrev_i32_e32 v129, 31, v128
	v_ashrrev_i32_e32 v131, 31, v130
	v_lshl_add_u64 v[128:129], v[128:129], 1, s[6:7]
	v_lshl_add_u64 v[130:131], v[130:131], 1, s[6:7]
	s_waitcnt lgkmcnt(0)
	v_add_f32_e32 v132, v132, v135
	v_fmamk_f32 v132, v132, 0x3c800000, v119
	v_rsq_f32_e32 v132, v132
	global_store_short v[128:129], v133, off sc1
	global_store_short v[130:131], v134, off sc1
	v_pk_mul_f32 v[128:129], v[70:71], v[132:133] op_sel_hi:[1,0]
	s_nop 0
	v_pk_mul_f32 v[72:73], v[72:73], v[128:129]
	s_cbranch_vccnz .LBB0_621
	global_load_dwordx2 v[128:129], v136, s[8:9]
	s_waitcnt vmcnt(0)
	v_pk_mul_f32 v[132:133], v[72:73], v[128:129] op_sel_hi:[0,1]
	v_pk_mul_f32 v[130:131], v[72:73], v[128:129] op_sel:[1,1] op_sel_hi:[1,0]
	v_pk_fma_f32 v[72:73], v[72:73], v[128:129], v[132:133] op_sel:[1,1,0] op_sel_hi:[1,0,1] neg_lo:[0,0,1] neg_hi:[0,0,1]
	s_nop 0
	v_add_f32_e32 v72, v130, v132
.LBB0_621:
	v_mov_b32_e32 v128, v22
	v_mov_b32_e32 v129, v6
	v_pk_mul_f32 v[128:129], v[128:129], v[128:129]
	v_add_u32_e32 v130, s74, v141
	v_add_f32_e32 v128, v128, v129
	ds_bpermute_b32 v129, v123, v128
	v_cvt_pk_bf16_f32 v133, v73, s0
	v_cvt_pk_bf16_f32 v134, v72, s0
	v_mov_b32_e32 v72, v6
	v_mov_b32_e32 v73, v22
	s_waitcnt lgkmcnt(0)
	v_add_f32_e32 v128, v128, v129
	ds_bpermute_b32 v129, v124, v128
	s_and_b64 vcc, exec, s[0:1]
	s_waitcnt lgkmcnt(0)
	v_add_f32_e32 v128, v128, v129
	ds_bpermute_b32 v129, v125, v128
	s_waitcnt lgkmcnt(0)
	v_add_f32_e32 v129, v128, v129
	ds_bpermute_b32 v131, v127, v129
	v_add_u32_e32 v128, v130, v81
	v_add_u32_e32 v130, v130, v82
	s_waitcnt lgkmcnt(0)
	v_add_f32_e32 v132, v129, v131
	ds_bpermute_b32 v135, v126, v132
	v_ashrrev_i32_e32 v129, 31, v128
	v_ashrrev_i32_e32 v131, 31, v130
	v_lshl_add_u64 v[128:129], v[128:129], 1, s[6:7]
	v_lshl_add_u64 v[130:131], v[130:131], 1, s[6:7]
	s_waitcnt lgkmcnt(0)
	v_add_f32_e32 v132, v132, v135
	v_fmamk_f32 v132, v132, 0x3c800000, v119
	v_rsq_f32_e32 v132, v132
	global_store_short v[128:129], v133, off sc1
	global_store_short v[130:131], v134, off sc1
	v_pk_mul_f32 v[128:129], v[70:71], v[132:133] op_sel_hi:[1,0]
	s_nop 0
	v_pk_mul_f32 v[72:73], v[72:73], v[128:129]
	s_cbranch_vccnz .LBB0_623
	global_load_dwordx2 v[128:129], v138, s[8:9]
	s_waitcnt vmcnt(0)
	v_pk_mul_f32 v[132:133], v[72:73], v[128:129] op_sel_hi:[0,1]
	v_pk_mul_f32 v[130:131], v[72:73], v[128:129] op_sel:[1,1] op_sel_hi:[1,0]
	v_pk_fma_f32 v[72:73], v[72:73], v[128:129], v[132:133] op_sel:[1,1,0] op_sel_hi:[1,0,1] neg_lo:[0,0,1] neg_hi:[0,0,1]
	s_nop 0
	v_add_f32_e32 v72, v130, v132
.LBB0_623:
	v_mov_b32_e32 v128, v23
	v_mov_b32_e32 v129, v7
	v_pk_mul_f32 v[128:129], v[128:129], v[128:129]
	v_add_u32_e32 v130, s74, v144
	v_add_f32_e32 v128, v128, v129
	ds_bpermute_b32 v129, v123, v128
	v_cvt_pk_bf16_f32 v133, v73, s0
	v_cvt_pk_bf16_f32 v134, v72, s0
	v_mov_b32_e32 v72, v7
	v_mov_b32_e32 v73, v23
	s_waitcnt lgkmcnt(0)
	v_add_f32_e32 v128, v128, v129
	ds_bpermute_b32 v129, v124, v128
	s_and_b64 vcc, exec, s[0:1]
	s_waitcnt lgkmcnt(0)
	v_add_f32_e32 v128, v128, v129
	ds_bpermute_b32 v129, v125, v128
	s_waitcnt lgkmcnt(0)
	v_add_f32_e32 v129, v128, v129
	ds_bpermute_b32 v131, v127, v129
	v_add_u32_e32 v128, v130, v81
	v_add_u32_e32 v130, v130, v82
	s_waitcnt lgkmcnt(0)
	v_add_f32_e32 v132, v129, v131
	ds_bpermute_b32 v135, v126, v132
	v_ashrrev_i32_e32 v129, 31, v128
	v_ashrrev_i32_e32 v131, 31, v130
	v_lshl_add_u64 v[128:129], v[128:129], 1, s[6:7]
	v_lshl_add_u64 v[130:131], v[130:131], 1, s[6:7]
	s_waitcnt lgkmcnt(0)
	v_add_f32_e32 v132, v132, v135
	v_fmamk_f32 v132, v132, 0x3c800000, v119
	v_rsq_f32_e32 v132, v132
	global_store_short v[128:129], v133, off sc1
	global_store_short v[130:131], v134, off sc1
	v_pk_mul_f32 v[128:129], v[70:71], v[132:133] op_sel_hi:[1,0]
	s_nop 0
	v_pk_mul_f32 v[72:73], v[72:73], v[128:129]
	s_cbranch_vccnz .LBB0_625
	global_load_dwordx2 v[128:129], v140, s[8:9]
	s_waitcnt vmcnt(0)
	v_pk_mul_f32 v[132:133], v[72:73], v[128:129] op_sel_hi:[0,1]
	v_pk_mul_f32 v[130:131], v[72:73], v[128:129] op_sel:[1,1] op_sel_hi:[1,0]
	v_pk_fma_f32 v[72:73], v[72:73], v[128:129], v[132:133] op_sel:[1,1,0] op_sel_hi:[1,0,1] neg_lo:[0,0,1] neg_hi:[0,0,1]
	s_nop 0
	v_add_f32_e32 v72, v130, v132
.LBB0_625:
	v_mov_b32_e32 v128, v24
	v_mov_b32_e32 v129, v8
	v_pk_mul_f32 v[128:129], v[128:129], v[128:129]
	v_add_u32_e32 v130, s74, v146
	v_add_f32_e32 v128, v128, v129
	ds_bpermute_b32 v129, v123, v128
	v_cvt_pk_bf16_f32 v133, v73, s0
	v_cvt_pk_bf16_f32 v134, v72, s0
	v_mov_b32_e32 v72, v8
	v_mov_b32_e32 v73, v24
	s_waitcnt lgkmcnt(0)
	v_add_f32_e32 v128, v128, v129
	ds_bpermute_b32 v129, v124, v128
	s_and_b64 vcc, exec, s[0:1]
	s_waitcnt lgkmcnt(0)
	v_add_f32_e32 v128, v128, v129
	ds_bpermute_b32 v129, v125, v128
	s_waitcnt lgkmcnt(0)
	v_add_f32_e32 v129, v128, v129
	ds_bpermute_b32 v131, v127, v129
	v_add_u32_e32 v128, v130, v81
	v_add_u32_e32 v130, v130, v82
	s_waitcnt lgkmcnt(0)
	v_add_f32_e32 v132, v129, v131
	ds_bpermute_b32 v135, v126, v132
	v_ashrrev_i32_e32 v129, 31, v128
	v_ashrrev_i32_e32 v131, 31, v130
	v_lshl_add_u64 v[128:129], v[128:129], 1, s[6:7]
	v_lshl_add_u64 v[130:131], v[130:131], 1, s[6:7]
	s_waitcnt lgkmcnt(0)
	v_add_f32_e32 v132, v132, v135
	v_fmamk_f32 v132, v132, 0x3c800000, v119
	v_rsq_f32_e32 v132, v132
	global_store_short v[128:129], v133, off sc1
	global_store_short v[130:131], v134, off sc1
	v_pk_mul_f32 v[128:129], v[70:71], v[132:133] op_sel_hi:[1,0]
	s_nop 0
	v_pk_mul_f32 v[72:73], v[72:73], v[128:129]
	s_cbranch_vccnz .LBB0_627
	global_load_dwordx2 v[128:129], v143, s[8:9]
	s_waitcnt vmcnt(0)
	v_pk_mul_f32 v[132:133], v[72:73], v[128:129] op_sel_hi:[0,1]
	v_pk_mul_f32 v[130:131], v[72:73], v[128:129] op_sel:[1,1] op_sel_hi:[1,0]
	v_pk_fma_f32 v[72:73], v[72:73], v[128:129], v[132:133] op_sel:[1,1,0] op_sel_hi:[1,0,1] neg_lo:[0,0,1] neg_hi:[0,0,1]
	s_nop 0
	v_add_f32_e32 v72, v130, v132
.LBB0_627:
	v_mov_b32_e32 v128, v25
	v_mov_b32_e32 v129, v9
	v_pk_mul_f32 v[128:129], v[128:129], v[128:129]
	v_add_u32_e32 v130, s74, v148
	v_add_f32_e32 v128, v128, v129
	ds_bpermute_b32 v129, v123, v128
	v_cvt_pk_bf16_f32 v133, v73, s0
	v_cvt_pk_bf16_f32 v134, v72, s0
	v_mov_b32_e32 v72, v9
	v_mov_b32_e32 v73, v25
	s_waitcnt lgkmcnt(0)
	v_add_f32_e32 v128, v128, v129
	ds_bpermute_b32 v129, v124, v128
	s_and_b64 vcc, exec, s[0:1]
	s_waitcnt lgkmcnt(0)
	v_add_f32_e32 v128, v128, v129
	ds_bpermute_b32 v129, v125, v128
	s_waitcnt lgkmcnt(0)
	v_add_f32_e32 v129, v128, v129
	ds_bpermute_b32 v131, v127, v129
	v_add_u32_e32 v128, v130, v81
	v_add_u32_e32 v130, v130, v82
	s_waitcnt lgkmcnt(0)
	v_add_f32_e32 v132, v129, v131
	ds_bpermute_b32 v135, v126, v132
	v_ashrrev_i32_e32 v129, 31, v128
	v_ashrrev_i32_e32 v131, 31, v130
	v_lshl_add_u64 v[128:129], v[128:129], 1, s[6:7]
	v_lshl_add_u64 v[130:131], v[130:131], 1, s[6:7]
	s_waitcnt lgkmcnt(0)
	v_add_f32_e32 v132, v132, v135
	v_fmamk_f32 v132, v132, 0x3c800000, v119
	v_rsq_f32_e32 v132, v132
	global_store_short v[128:129], v133, off sc1
	global_store_short v[130:131], v134, off sc1
	v_pk_mul_f32 v[128:129], v[70:71], v[132:133] op_sel_hi:[1,0]
	s_nop 0
	v_pk_mul_f32 v[72:73], v[72:73], v[128:129]
	s_cbranch_vccnz .LBB0_629
	global_load_dwordx2 v[128:129], v145, s[8:9]
	s_waitcnt vmcnt(0)
	v_pk_mul_f32 v[132:133], v[72:73], v[128:129] op_sel_hi:[0,1]
	v_pk_mul_f32 v[130:131], v[72:73], v[128:129] op_sel:[1,1] op_sel_hi:[1,0]
	v_pk_fma_f32 v[72:73], v[72:73], v[128:129], v[132:133] op_sel:[1,1,0] op_sel_hi:[1,0,1] neg_lo:[0,0,1] neg_hi:[0,0,1]
	s_nop 0
	v_add_f32_e32 v72, v130, v132
.LBB0_629:
	v_mov_b32_e32 v128, v26
	v_mov_b32_e32 v129, v10
	v_pk_mul_f32 v[128:129], v[128:129], v[128:129]
	v_add_u32_e32 v130, s74, v150
	v_add_f32_e32 v128, v128, v129
	ds_bpermute_b32 v129, v123, v128
	v_cvt_pk_bf16_f32 v133, v73, s0
	v_cvt_pk_bf16_f32 v134, v72, s0
	v_mov_b32_e32 v72, v10
	v_mov_b32_e32 v73, v26
	s_waitcnt lgkmcnt(0)
	v_add_f32_e32 v128, v128, v129
	ds_bpermute_b32 v129, v124, v128
	s_and_b64 vcc, exec, s[0:1]
	s_waitcnt lgkmcnt(0)
	v_add_f32_e32 v128, v128, v129
	ds_bpermute_b32 v129, v125, v128
	s_waitcnt lgkmcnt(0)
	v_add_f32_e32 v129, v128, v129
	ds_bpermute_b32 v131, v127, v129
	v_add_u32_e32 v128, v130, v81
	v_add_u32_e32 v130, v130, v82
	s_waitcnt lgkmcnt(0)
	v_add_f32_e32 v132, v129, v131
	ds_bpermute_b32 v135, v126, v132
	v_ashrrev_i32_e32 v129, 31, v128
	v_ashrrev_i32_e32 v131, 31, v130
	v_lshl_add_u64 v[128:129], v[128:129], 1, s[6:7]
	v_lshl_add_u64 v[130:131], v[130:131], 1, s[6:7]
	s_waitcnt lgkmcnt(0)
	v_add_f32_e32 v132, v132, v135
	v_fmamk_f32 v132, v132, 0x3c800000, v119
	v_rsq_f32_e32 v132, v132
	global_store_short v[128:129], v133, off sc1
	global_store_short v[130:131], v134, off sc1
	v_pk_mul_f32 v[128:129], v[70:71], v[132:133] op_sel_hi:[1,0]
	s_nop 0
	v_pk_mul_f32 v[72:73], v[72:73], v[128:129]
	s_cbranch_vccnz .LBB0_631
	global_load_dwordx2 v[128:129], v147, s[8:9]
	s_waitcnt vmcnt(0)
	v_pk_mul_f32 v[132:133], v[72:73], v[128:129] op_sel_hi:[0,1]
	v_pk_mul_f32 v[130:131], v[72:73], v[128:129] op_sel:[1,1] op_sel_hi:[1,0]
	v_pk_fma_f32 v[72:73], v[72:73], v[128:129], v[132:133] op_sel:[1,1,0] op_sel_hi:[1,0,1] neg_lo:[0,0,1] neg_hi:[0,0,1]
	s_nop 0
	v_add_f32_e32 v72, v130, v132
.LBB0_631:
	v_mov_b32_e32 v128, v27
	v_mov_b32_e32 v129, v11
	v_pk_mul_f32 v[128:129], v[128:129], v[128:129]
	v_add_u32_e32 v130, s74, v152
	v_add_f32_e32 v128, v128, v129
	ds_bpermute_b32 v129, v123, v128
	v_cvt_pk_bf16_f32 v133, v73, s0
	v_cvt_pk_bf16_f32 v134, v72, s0
	v_mov_b32_e32 v72, v11
	v_mov_b32_e32 v73, v27
	s_waitcnt lgkmcnt(0)
	v_add_f32_e32 v128, v128, v129
	ds_bpermute_b32 v129, v124, v128
	s_and_b64 vcc, exec, s[0:1]
	s_waitcnt lgkmcnt(0)
	v_add_f32_e32 v128, v128, v129
	ds_bpermute_b32 v129, v125, v128
	s_waitcnt lgkmcnt(0)
	v_add_f32_e32 v129, v128, v129
	ds_bpermute_b32 v131, v127, v129
	v_add_u32_e32 v128, v130, v81
	v_add_u32_e32 v130, v130, v82
	s_waitcnt lgkmcnt(0)
	v_add_f32_e32 v132, v129, v131
	ds_bpermute_b32 v135, v126, v132
	v_ashrrev_i32_e32 v129, 31, v128
	v_ashrrev_i32_e32 v131, 31, v130
	v_lshl_add_u64 v[128:129], v[128:129], 1, s[6:7]
	v_lshl_add_u64 v[130:131], v[130:131], 1, s[6:7]
	s_waitcnt lgkmcnt(0)
	v_add_f32_e32 v132, v132, v135
	v_fmamk_f32 v132, v132, 0x3c800000, v119
	v_rsq_f32_e32 v132, v132
	global_store_short v[128:129], v133, off sc1
	global_store_short v[130:131], v134, off sc1
	v_pk_mul_f32 v[128:129], v[70:71], v[132:133] op_sel_hi:[1,0]
	s_nop 0
	v_pk_mul_f32 v[72:73], v[72:73], v[128:129]
	s_cbranch_vccnz .LBB0_633
	global_load_dwordx2 v[128:129], v149, s[8:9]
	s_waitcnt vmcnt(0)
	v_pk_mul_f32 v[132:133], v[72:73], v[128:129] op_sel_hi:[0,1]
	v_pk_mul_f32 v[130:131], v[72:73], v[128:129] op_sel:[1,1] op_sel_hi:[1,0]
	v_pk_fma_f32 v[72:73], v[72:73], v[128:129], v[132:133] op_sel:[1,1,0] op_sel_hi:[1,0,1] neg_lo:[0,0,1] neg_hi:[0,0,1]
	s_nop 0
	v_add_f32_e32 v72, v130, v132
.LBB0_633:
	v_mov_b32_e32 v128, v28
	v_mov_b32_e32 v129, v12
	v_pk_mul_f32 v[128:129], v[128:129], v[128:129]
	v_add_u32_e32 v130, s74, v154
	v_add_f32_e32 v128, v128, v129
	ds_bpermute_b32 v129, v123, v128
	v_cvt_pk_bf16_f32 v133, v73, s0
	v_cvt_pk_bf16_f32 v134, v72, s0
	v_mov_b32_e32 v72, v12
	v_mov_b32_e32 v73, v28
	s_waitcnt lgkmcnt(0)
	v_add_f32_e32 v128, v128, v129
	ds_bpermute_b32 v129, v124, v128
	s_and_b64 vcc, exec, s[0:1]
	s_waitcnt lgkmcnt(0)
	v_add_f32_e32 v128, v128, v129
	ds_bpermute_b32 v129, v125, v128
	s_waitcnt lgkmcnt(0)
	v_add_f32_e32 v129, v128, v129
	ds_bpermute_b32 v131, v127, v129
	v_add_u32_e32 v128, v130, v81
	v_add_u32_e32 v130, v130, v82
	s_waitcnt lgkmcnt(0)
	v_add_f32_e32 v132, v129, v131
	ds_bpermute_b32 v135, v126, v132
	v_ashrrev_i32_e32 v129, 31, v128
	v_ashrrev_i32_e32 v131, 31, v130
	v_lshl_add_u64 v[128:129], v[128:129], 1, s[6:7]
	v_lshl_add_u64 v[130:131], v[130:131], 1, s[6:7]
	s_waitcnt lgkmcnt(0)
	v_add_f32_e32 v132, v132, v135
	v_fmamk_f32 v132, v132, 0x3c800000, v119
	v_rsq_f32_e32 v132, v132
	global_store_short v[128:129], v133, off sc1
	global_store_short v[130:131], v134, off sc1
	v_pk_mul_f32 v[128:129], v[70:71], v[132:133] op_sel_hi:[1,0]
	s_nop 0
	v_pk_mul_f32 v[72:73], v[72:73], v[128:129]
	s_cbranch_vccnz .LBB0_635
	global_load_dwordx2 v[128:129], v151, s[8:9]
	s_waitcnt vmcnt(0)
	v_pk_mul_f32 v[132:133], v[72:73], v[128:129] op_sel_hi:[0,1]
	v_pk_mul_f32 v[130:131], v[72:73], v[128:129] op_sel:[1,1] op_sel_hi:[1,0]
	v_pk_fma_f32 v[72:73], v[72:73], v[128:129], v[132:133] op_sel:[1,1,0] op_sel_hi:[1,0,1] neg_lo:[0,0,1] neg_hi:[0,0,1]
	s_nop 0
	v_add_f32_e32 v72, v130, v132
.LBB0_635:
	v_mov_b32_e32 v128, v29
	v_mov_b32_e32 v129, v13
	v_pk_mul_f32 v[128:129], v[128:129], v[128:129]
	v_add_u32_e32 v130, s74, v156
	v_add_f32_e32 v128, v128, v129
	ds_bpermute_b32 v129, v123, v128
	v_cvt_pk_bf16_f32 v133, v73, s0
	v_cvt_pk_bf16_f32 v134, v72, s0
	v_mov_b32_e32 v72, v13
	v_mov_b32_e32 v73, v29
	s_waitcnt lgkmcnt(0)
	v_add_f32_e32 v128, v128, v129
	ds_bpermute_b32 v129, v124, v128
	s_and_b64 vcc, exec, s[0:1]
	s_waitcnt lgkmcnt(0)
	v_add_f32_e32 v128, v128, v129
	ds_bpermute_b32 v129, v125, v128
	s_waitcnt lgkmcnt(0)
	v_add_f32_e32 v129, v128, v129
	ds_bpermute_b32 v131, v127, v129
	v_add_u32_e32 v128, v130, v81
	v_add_u32_e32 v130, v130, v82
	s_waitcnt lgkmcnt(0)
	v_add_f32_e32 v132, v129, v131
	ds_bpermute_b32 v135, v126, v132
	v_ashrrev_i32_e32 v129, 31, v128
	v_ashrrev_i32_e32 v131, 31, v130
	v_lshl_add_u64 v[128:129], v[128:129], 1, s[6:7]
	v_lshl_add_u64 v[130:131], v[130:131], 1, s[6:7]
	s_waitcnt lgkmcnt(0)
	v_add_f32_e32 v132, v132, v135
	v_fmamk_f32 v132, v132, 0x3c800000, v119
	v_rsq_f32_e32 v132, v132
	global_store_short v[128:129], v133, off sc1
	global_store_short v[130:131], v134, off sc1
	v_pk_mul_f32 v[128:129], v[70:71], v[132:133] op_sel_hi:[1,0]
	s_nop 0
	v_pk_mul_f32 v[72:73], v[72:73], v[128:129]
	s_cbranch_vccnz .LBB0_637
	global_load_dwordx2 v[128:129], v153, s[8:9]
	s_waitcnt vmcnt(0)
	v_pk_mul_f32 v[132:133], v[72:73], v[128:129] op_sel_hi:[0,1]
	v_pk_mul_f32 v[130:131], v[72:73], v[128:129] op_sel:[1,1] op_sel_hi:[1,0]
	v_pk_fma_f32 v[72:73], v[72:73], v[128:129], v[132:133] op_sel:[1,1,0] op_sel_hi:[1,0,1] neg_lo:[0,0,1] neg_hi:[0,0,1]
	s_nop 0
	v_add_f32_e32 v72, v130, v132
.LBB0_637:
	v_mov_b32_e32 v128, v30
	v_mov_b32_e32 v129, v14
	v_pk_mul_f32 v[128:129], v[128:129], v[128:129]
	v_add_u32_e32 v130, s74, v157
	v_add_f32_e32 v128, v128, v129
	ds_bpermute_b32 v129, v123, v128
	v_cvt_pk_bf16_f32 v133, v73, s0
	v_cvt_pk_bf16_f32 v134, v72, s0
	v_mov_b32_e32 v72, v14
	v_mov_b32_e32 v73, v30
	s_waitcnt lgkmcnt(0)
	v_add_f32_e32 v128, v128, v129
	ds_bpermute_b32 v129, v124, v128
	s_and_b64 vcc, exec, s[0:1]
	s_waitcnt lgkmcnt(0)
	v_add_f32_e32 v128, v128, v129
	ds_bpermute_b32 v129, v125, v128
	s_waitcnt lgkmcnt(0)
	v_add_f32_e32 v129, v128, v129
	ds_bpermute_b32 v131, v127, v129
	v_add_u32_e32 v128, v130, v81
	v_add_u32_e32 v130, v130, v82
	s_waitcnt lgkmcnt(0)
	v_add_f32_e32 v132, v129, v131
	ds_bpermute_b32 v135, v126, v132
	v_ashrrev_i32_e32 v129, 31, v128
	v_ashrrev_i32_e32 v131, 31, v130
	v_lshl_add_u64 v[128:129], v[128:129], 1, s[6:7]
	v_lshl_add_u64 v[130:131], v[130:131], 1, s[6:7]
	s_waitcnt lgkmcnt(0)
	v_add_f32_e32 v132, v132, v135
	v_fmamk_f32 v132, v132, 0x3c800000, v119
	v_rsq_f32_e32 v132, v132
	global_store_short v[128:129], v133, off sc1
	global_store_short v[130:131], v134, off sc1
	v_pk_mul_f32 v[128:129], v[70:71], v[132:133] op_sel_hi:[1,0]
	s_nop 0
	v_pk_mul_f32 v[72:73], v[72:73], v[128:129]
	s_cbranch_vccnz .LBB0_639
	global_load_dwordx2 v[128:129], v155, s[8:9]
	s_waitcnt vmcnt(0)
	v_pk_mul_f32 v[132:133], v[72:73], v[128:129] op_sel_hi:[0,1]
	v_pk_mul_f32 v[130:131], v[72:73], v[128:129] op_sel:[1,1] op_sel_hi:[1,0]
	v_pk_fma_f32 v[72:73], v[72:73], v[128:129], v[132:133] op_sel:[1,1,0] op_sel_hi:[1,0,1] neg_lo:[0,0,1] neg_hi:[0,0,1]
	s_nop 0
	v_add_f32_e32 v72, v130, v132
.LBB0_639:
	v_mov_b32_e32 v128, v31
	v_mov_b32_e32 v129, v15
	v_pk_mul_f32 v[128:129], v[128:129], v[128:129]
	v_cvt_pk_bf16_f32 v130, v72, s0
	v_add_f32_e32 v128, v128, v129
	ds_bpermute_b32 v123, v123, v128
	v_cvt_pk_bf16_f32 v129, v73, s0
	v_mov_b32_e32 v72, v15
	v_mov_b32_e32 v73, v31
	s_and_b64 vcc, exec, s[0:1]
	s_waitcnt lgkmcnt(0)
	v_add_f32_e32 v123, v128, v123
	ds_bpermute_b32 v124, v124, v123
	s_waitcnt lgkmcnt(0)
	v_add_f32_e32 v123, v123, v124
	ds_bpermute_b32 v124, v125, v123
	v_add_u32_e32 v125, s74, v158
	s_waitcnt lgkmcnt(0)
	v_add_f32_e32 v123, v123, v124
	ds_bpermute_b32 v127, v127, v123
	v_add_u32_e32 v124, v125, v81
	s_waitcnt lgkmcnt(0)
	v_add_f32_e32 v123, v123, v127
	ds_bpermute_b32 v128, v126, v123
	v_add_u32_e32 v126, v125, v82
	v_ashrrev_i32_e32 v125, 31, v124
	v_ashrrev_i32_e32 v127, 31, v126
	v_lshl_add_u64 v[124:125], v[124:125], 1, s[6:7]
	s_waitcnt lgkmcnt(0)
	v_add_f32_e32 v123, v123, v128
	v_fmamk_f32 v123, v123, 0x3c800000, v119
	v_rsq_f32_e32 v128, v123
	v_lshl_add_u64 v[126:127], v[126:127], 1, s[6:7]
	global_store_short v[124:125], v129, off sc1
	global_store_short v[126:127], v130, off sc1
	v_pk_mul_f32 v[70:71], v[70:71], v[128:129] op_sel_hi:[1,0]
	s_nop 0
	v_pk_mul_f32 v[70:71], v[72:73], v[70:71]
	s_cbranch_vccnz .LBB0_641
	global_load_dwordx2 v[72:73], v142, s[8:9]
	s_waitcnt vmcnt(0)
	v_pk_mul_f32 v[126:127], v[70:71], v[72:73] op_sel_hi:[0,1]
	v_pk_mul_f32 v[124:125], v[70:71], v[72:73] op_sel:[1,1] op_sel_hi:[1,0]
	v_pk_fma_f32 v[70:71], v[70:71], v[72:73], v[126:127] op_sel:[1,1,0] op_sel_hi:[1,0,1] neg_lo:[0,0,1] neg_hi:[0,0,1]
	s_nop 0
	v_add_f32_e32 v70, v124, v126
.LBB0_641:
	v_add_u32_e32 v123, s74, v159
	v_add_u32_e32 v72, v123, v81
	v_ashrrev_i32_e32 v73, 31, v72
	v_cvt_pk_bf16_f32 v71, v71, s0
	v_lshl_add_u64 v[72:73], v[72:73], 1, s[6:7]
	global_store_short v[72:73], v71, off sc1
	v_add_u32_e32 v72, v123, v82
	s_mov_b64 s[0:1], 0
.LBB0_642:
	s_and_b64 vcc, exec, s[0:1]
	s_cbranch_vccz .LBB0_575
	v_and_b32_e32 v71, 64, v122
	v_xor_b32_e32 v70, 1, v122
	v_add_u32_e32 v71, 64, v71
	v_mul_f32_e32 v72, v32, v32
	v_cmp_lt_i32_e32 vcc, v70, v71
	v_fmac_f32_e32 v72, v48, v48
	v_fmac_f32_e32 v72, v16, v16
	v_cndmask_b32_e32 v70, v122, v70, vcc
	v_lshlrev_b32_e32 v132, 2, v70
	v_fmac_f32_e32 v72, v0, v0
	ds_bpermute_b32 v73, v132, v72
	v_xor_b32_e32 v70, 2, v122
	v_cmp_lt_i32_e32 vcc, v70, v71
	v_mul_f32_e32 v123, v33, v33
	v_fmac_f32_e32 v123, v49, v49
	v_cndmask_b32_e32 v70, v122, v70, vcc
	v_lshlrev_b32_e32 v133, 2, v70
	s_waitcnt lgkmcnt(0)
	v_add_f32_e32 v72, v72, v73
	v_xor_b32_e32 v70, 4, v122
	ds_bpermute_b32 v73, v133, v72
	v_cmp_lt_i32_e32 vcc, v70, v71
	v_fmac_f32_e32 v123, v17, v17
	v_fmac_f32_e32 v123, v1, v1
	v_cndmask_b32_e32 v70, v122, v70, vcc
	v_lshlrev_b32_e32 v135, 2, v70
	v_xor_b32_e32 v70, 8, v122
	v_cmp_lt_i32_e32 vcc, v70, v71
	s_waitcnt lgkmcnt(0)
	v_add_f32_e32 v72, v72, v73
	ds_bpermute_b32 v73, v135, v72
	v_cndmask_b32_e32 v70, v122, v70, vcc
	v_lshlrev_b32_e32 v136, 2, v70
	v_xor_b32_e32 v70, 16, v122
	ds_bpermute_b32 v124, v132, v123
	v_cmp_lt_i32_e32 vcc, v70, v71
	v_mul_f32_e32 v128, v40, v40
	v_fmac_f32_e32 v128, v56, v56
	v_cndmask_b32_e32 v70, v122, v70, vcc
	v_mul_f32_e32 v122, v34, v34
	v_fmac_f32_e32 v122, v50, v50
	v_fmac_f32_e32 v122, v18, v18
	v_lshlrev_b32_e32 v137, 2, v70
	s_waitcnt lgkmcnt(1)
	v_add_f32_e32 v70, v72, v73
	s_waitcnt lgkmcnt(0)
	v_add_f32_e32 v72, v123, v124
	v_fmac_f32_e32 v122, v2, v2
	ds_bpermute_b32 v71, v136, v70
	ds_bpermute_b32 v73, v133, v72
	ds_bpermute_b32 v123, v132, v122
	v_fmac_f32_e32 v128, v24, v24
	v_fmac_f32_e32 v128, v8, v8
	s_waitcnt lgkmcnt(2)
	v_add_f32_e32 v70, v70, v71
	s_waitcnt lgkmcnt(1)
	v_add_f32_e32 v72, v72, v73
	s_waitcnt lgkmcnt(0)
	v_add_f32_e32 v122, v122, v123
	ds_bpermute_b32 v71, v137, v70
	ds_bpermute_b32 v73, v135, v72
	ds_bpermute_b32 v123, v133, v122
	ds_bpermute_b32 v129, v132, v128
	v_mul_f32_e32 v141, v46, v46
	s_waitcnt lgkmcnt(3)
	v_add_f32_e32 v70, v70, v71
	s_waitcnt lgkmcnt(2)
	v_add_f32_e32 v71, v72, v73
	s_waitcnt lgkmcnt(1)
	v_add_f32_e32 v73, v122, v123
	v_mul_f32_e32 v123, v35, v35
	v_fmac_f32_e32 v123, v51, v51
	v_fmac_f32_e32 v123, v19, v19
	v_fmac_f32_e32 v123, v3, v3
	ds_bpermute_b32 v72, v136, v71
	ds_bpermute_b32 v122, v135, v73
	ds_bpermute_b32 v124, v132, v123
	v_fmamk_f32 v70, v70, 0x3c000000, v119
	s_waitcnt lgkmcnt(3)
	v_add_f32_e32 v128, v128, v129
	s_waitcnt lgkmcnt(2)
	v_add_f32_e32 v72, v71, v72
	s_waitcnt lgkmcnt(1)
	v_add_f32_e32 v73, v73, v122
	s_waitcnt lgkmcnt(0)
	v_add_f32_e32 v123, v123, v124
	ds_bpermute_b32 v125, v137, v72
	ds_bpermute_b32 v122, v136, v73
	ds_bpermute_b32 v124, v133, v123
	v_rsq_f32_e32 v71, v70
	ds_bpermute_b32 v129, v133, v128
	s_waitcnt lgkmcnt(3)
	v_add_f32_e32 v70, v72, v125
	s_waitcnt lgkmcnt(2)
	v_add_f32_e32 v72, v73, v122
	s_waitcnt lgkmcnt(1)
	v_add_f32_e32 v122, v123, v124
	ds_bpermute_b32 v73, v137, v72
	ds_bpermute_b32 v123, v135, v122
	v_mul_f32_e32 v125, v37, v37
	v_fmac_f32_e32 v125, v53, v53
	v_fmac_f32_e32 v125, v21, v21
	s_waitcnt lgkmcnt(1)
	v_add_f32_e32 v72, v72, v73
	s_waitcnt lgkmcnt(0)
	v_add_f32_e32 v73, v122, v123
	v_mul_f32_e32 v123, v36, v36
	v_fmac_f32_e32 v123, v52, v52
	v_fmac_f32_e32 v123, v20, v20
	v_fmac_f32_e32 v123, v4, v4
	v_fmac_f32_e32 v125, v5, v5
	ds_bpermute_b32 v122, v136, v73
	ds_bpermute_b32 v124, v132, v123
	ds_bpermute_b32 v126, v132, v125
	v_fmamk_f32 v72, v72, 0x3c000000, v119
	v_mul_f32_e32 v143, v47, v47
	s_waitcnt lgkmcnt(2)
	v_add_f32_e32 v122, v73, v122
	s_waitcnt lgkmcnt(1)
	v_add_f32_e32 v123, v123, v124
	s_waitcnt lgkmcnt(0)
	v_add_f32_e32 v125, v125, v126
	ds_bpermute_b32 v127, v137, v122
	ds_bpermute_b32 v124, v133, v123
	ds_bpermute_b32 v126, v133, v125
	v_rsq_f32_e32 v73, v72
	v_fmac_f32_e32 v141, v62, v62
	s_waitcnt lgkmcnt(2)
	v_add_f32_e32 v72, v122, v127
	s_waitcnt lgkmcnt(1)
	v_add_f32_e32 v122, v123, v124
	s_waitcnt lgkmcnt(0)
	v_add_f32_e32 v124, v125, v126
	ds_bpermute_b32 v123, v135, v122
	ds_bpermute_b32 v125, v135, v124
	v_mul_f32_e32 v126, v38, v38
	v_fmac_f32_e32 v126, v54, v54
	v_fmac_f32_e32 v126, v22, v22
	s_waitcnt lgkmcnt(1)
	v_add_f32_e32 v122, v122, v123
	s_waitcnt lgkmcnt(0)
	v_add_f32_e32 v124, v124, v125
	v_fmac_f32_e32 v126, v6, v6
	ds_bpermute_b32 v123, v136, v122
	ds_bpermute_b32 v125, v136, v124
	ds_bpermute_b32 v127, v132, v126
	v_fmac_f32_e32 v143, v63, v63
	v_fmac_f32_e32 v141, v30, v30
	s_waitcnt lgkmcnt(2)
	v_add_f32_e32 v122, v122, v123
	s_waitcnt lgkmcnt(1)
	v_add_f32_e32 v124, v124, v125
	s_waitcnt lgkmcnt(0)
	v_add_f32_e32 v126, v126, v127
	ds_bpermute_b32 v123, v137, v122
	ds_bpermute_b32 v125, v137, v124
	ds_bpermute_b32 v127, v133, v126
	v_fmac_f32_e32 v141, v14, v14
	ds_bpermute_b32 v142, v132, v141
	s_waitcnt lgkmcnt(3)
	v_add_f32_e32 v122, v122, v123
	s_waitcnt lgkmcnt(2)
	v_add_f32_e32 v123, v124, v125
	s_waitcnt lgkmcnt(1)
	v_add_f32_e32 v124, v126, v127
	v_mul_f32_e32 v126, v39, v39
	v_fmac_f32_e32 v126, v55, v55
	v_fmac_f32_e32 v126, v23, v23
	v_fmac_f32_e32 v126, v7, v7
	ds_bpermute_b32 v125, v135, v124
	ds_bpermute_b32 v127, v132, v126
	s_mulk_i32 s72, 0xc0
	v_fmamk_f32 v70, v70, 0x3c000000, v119
	v_rsq_f32_e32 v70, v70
	s_waitcnt lgkmcnt(1)
	v_add_f32_e32 v124, v124, v125
	s_waitcnt lgkmcnt(0)
	v_add_f32_e32 v126, v126, v127
	ds_bpermute_b32 v125, v136, v124
	ds_bpermute_b32 v127, v133, v126
	v_mul_f32_e32 v49, v49, v70
	v_fmamk_f32 v72, v72, 0x3c000000, v119
	v_rsq_f32_e32 v72, v72
	s_waitcnt lgkmcnt(1)
	v_add_f32_e32 v124, v124, v125
	s_waitcnt lgkmcnt(0)
	v_add_f32_e32 v126, v126, v127
	ds_bpermute_b32 v125, v137, v124
	ds_bpermute_b32 v127, v135, v126
	v_fmamk_f32 v122, v122, 0x3c000000, v119
	v_rsq_f32_e32 v122, v122
	v_fmamk_f32 v123, v123, 0x3c000000, v119
	s_waitcnt lgkmcnt(1)
	v_add_f32_e32 v124, v124, v125
	s_waitcnt lgkmcnt(0)
	v_add_f32_e32 v125, v126, v127
	v_add_f32_e32 v127, v128, v129
	v_mul_f32_e32 v129, v41, v41
	v_fmac_f32_e32 v129, v57, v57
	v_fmac_f32_e32 v129, v25, v25
	v_fmac_f32_e32 v129, v9, v9
	ds_bpermute_b32 v126, v136, v125
	ds_bpermute_b32 v130, v132, v129
	ds_bpermute_b32 v128, v135, v127
	v_rsq_f32_e32 v123, v123
	v_fmamk_f32 v124, v124, 0x3c000000, v119
	s_waitcnt lgkmcnt(2)
	v_add_f32_e32 v125, v125, v126
	s_waitcnt lgkmcnt(1)
	v_add_f32_e32 v129, v129, v130
	ds_bpermute_b32 v126, v137, v125
	s_waitcnt lgkmcnt(1)
	v_add_f32_e32 v127, v127, v128
	ds_bpermute_b32 v130, v133, v129
	ds_bpermute_b32 v128, v136, v127
	v_rsq_f32_e32 v124, v124
	s_waitcnt lgkmcnt(2)
	v_add_f32_e32 v125, v125, v126
	v_fmamk_f32 v125, v125, 0x3c000000, v119
	s_waitcnt lgkmcnt(1)
	v_add_f32_e32 v126, v129, v130
	s_waitcnt lgkmcnt(0)
	v_add_f32_e32 v127, v127, v128
	ds_bpermute_b32 v128, v135, v126
	v_mul_f32_e32 v129, v42, v42
	v_fmac_f32_e32 v129, v58, v58
	v_fmac_f32_e32 v129, v26, v26
	v_fmac_f32_e32 v129, v10, v10
	s_waitcnt lgkmcnt(0)
	v_add_f32_e32 v128, v126, v128
	ds_bpermute_b32 v130, v132, v129
	ds_bpermute_b32 v134, v136, v128
	v_rsq_f32_e32 v126, v125
	ds_bpermute_b32 v131, v137, v127
	v_mul_f32_e32 v32, v32, v71
	s_waitcnt lgkmcnt(2)
	v_add_f32_e32 v125, v129, v130
	s_waitcnt lgkmcnt(1)
	v_add_f32_e32 v128, v128, v134
	v_mul_f32_e32 v134, v44, v44
	ds_bpermute_b32 v129, v133, v125
	v_fmac_f32_e32 v134, v60, v60
	v_fmac_f32_e32 v134, v28, v28
	v_fmac_f32_e32 v134, v12, v12
	ds_bpermute_b32 v130, v137, v128
	ds_bpermute_b32 v138, v132, v134
	s_waitcnt lgkmcnt(2)
	v_add_f32_e32 v129, v125, v129
	v_add_f32_e32 v127, v127, v131
	ds_bpermute_b32 v131, v135, v129
	s_waitcnt lgkmcnt(2)
	v_add_f32_e32 v125, v128, v130
	v_mul_f32_e32 v130, v43, v43
	s_waitcnt lgkmcnt(1)
	v_add_f32_e32 v138, v134, v138
	global_load_dword v134, v121, s[66:67]
	v_fmac_f32_e32 v130, v59, v59
	v_fmac_f32_e32 v130, v27, v27
	s_waitcnt lgkmcnt(0)
	v_add_f32_e32 v128, v129, v131
	v_fmac_f32_e32 v130, v11, v11
	ds_bpermute_b32 v129, v136, v128
	ds_bpermute_b32 v131, v132, v130
	ds_bpermute_b32 v139, v133, v138
	v_fmamk_f32 v127, v127, 0x3c000000, v119
	v_rsq_f32_e32 v127, v127
	s_waitcnt lgkmcnt(2)
	v_add_f32_e32 v128, v128, v129
	s_waitcnt lgkmcnt(1)
	v_add_f32_e32 v130, v130, v131
	ds_bpermute_b32 v129, v137, v128
	ds_bpermute_b32 v131, v133, v130
	v_fmamk_f32 v125, v125, 0x3c000000, v119
	v_rsq_f32_e32 v125, v125
	v_mul_f32_e32 v16, v16, v71
	s_waitcnt lgkmcnt(1)
	v_add_f32_e32 v128, v128, v129
	s_waitcnt lgkmcnt(0)
	v_add_f32_e32 v129, v130, v131
	v_add_f32_e32 v131, v138, v139
	ds_bpermute_b32 v130, v135, v129
	ds_bpermute_b32 v138, v135, v131
	v_mul_f32_e32 v139, v45, v45
	v_fmac_f32_e32 v139, v61, v61
	v_fmac_f32_e32 v139, v29, v29
	s_waitcnt lgkmcnt(1)
	v_add_f32_e32 v129, v129, v130
	s_waitcnt lgkmcnt(0)
	v_add_f32_e32 v131, v131, v138
	ds_bpermute_b32 v130, v136, v129
	ds_bpermute_b32 v138, v136, v131
	v_fmac_f32_e32 v139, v13, v13
	ds_bpermute_b32 v140, v132, v139
	v_fmamk_f32 v128, v128, 0x3c000000, v119
	s_waitcnt lgkmcnt(2)
	v_add_f32_e32 v129, v129, v130
	s_waitcnt lgkmcnt(1)
	v_add_f32_e32 v131, v131, v138
	ds_bpermute_b32 v130, v137, v129
	ds_bpermute_b32 v138, v137, v131
	s_waitcnt lgkmcnt(2)
	v_add_f32_e32 v139, v139, v140
	ds_bpermute_b32 v140, v133, v139
	v_rsq_f32_e32 v128, v128
	s_waitcnt lgkmcnt(2)
	v_add_f32_e32 v129, v129, v130
	s_waitcnt lgkmcnt(1)
	v_add_f32_e32 v138, v131, v138
	v_mov_b32_e32 v130, v31
	v_mov_b32_e32 v131, v15
	v_pk_mul_f32 v[130:131], v[130:131], v[130:131]
	s_waitcnt lgkmcnt(0)
	v_add_f32_e32 v139, v139, v140
	v_add_f32_e32 v130, v143, v130
	v_add_f32_e32 v130, v130, v131
	ds_bpermute_b32 v140, v135, v139
	ds_bpermute_b32 v131, v132, v130
	v_fmamk_f32 v129, v129, 0x3c000000, v119
	v_rsq_f32_e32 v129, v129
	v_mul_f32_e32 v0, v0, v71
	s_waitcnt lgkmcnt(1)
	v_add_f32_e32 v132, v139, v140
	v_add_f32_e32 v139, v141, v142
	s_waitcnt lgkmcnt(0)
	v_add_f32_e32 v130, v130, v131
	ds_bpermute_b32 v140, v133, v139
	ds_bpermute_b32 v131, v133, v130
	v_fmamk_f32 v133, v138, 0x3c000000, v119
	ds_bpermute_b32 v141, v136, v132
	s_waitcnt lgkmcnt(2)
	v_add_f32_e32 v138, v139, v140
	s_waitcnt lgkmcnt(1)
	v_add_f32_e32 v130, v130, v131
	ds_bpermute_b32 v139, v135, v138
	ds_bpermute_b32 v131, v135, v130
	s_waitcnt lgkmcnt(2)
	v_add_f32_e32 v140, v132, v141
	ds_bpermute_b32 v135, v137, v140
	v_rsq_f32_e32 v132, v133
	s_waitcnt lgkmcnt(2)
	v_add_f32_e32 v138, v138, v139
	s_waitcnt lgkmcnt(1)
	v_add_f32_e32 v130, v130, v131
	ds_bpermute_b32 v139, v136, v138
	ds_bpermute_b32 v131, v136, v130
	s_waitcnt lgkmcnt(2)
	v_add_f32_e32 v133, v140, v135
	v_fmamk_f32 v133, v133, 0x3c000000, v119
	v_rsq_f32_e32 v133, v133
	s_waitcnt lgkmcnt(1)
	v_add_f32_e32 v135, v138, v139
	s_waitcnt lgkmcnt(0)
	v_add_f32_e32 v130, v130, v131
	ds_bpermute_b32 v136, v137, v135
	ds_bpermute_b32 v137, v137, v130
	s_waitcnt vmcnt(0)
	v_mul_f32_e32 v49, v49, v134
	s_waitcnt lgkmcnt(1)
	v_add_f32_e32 v131, v135, v136
	s_waitcnt lgkmcnt(0)
	v_add_f32_e32 v130, v130, v137
	v_mul_f32_e32 v137, v48, v71
	global_load_dword v48, v121, s[66:67] offset:128
	global_load_dword v138, v121, s[66:67] offset:256
	s_nop 0
	global_load_dword v121, v121, s[66:67] offset:384
	v_add_u32_e32 v136, s73, v80
	v_or_b32_e32 v135, s72, v64
	v_mul_lo_u32 v140, v136, s70
	v_mul_f32_e32 v137, v137, v134
	v_add_u32_e32 v136, v140, v135
	v_cvt_pk_bf16_f32 v139, v137, s0
	v_ashrrev_i32_e32 v137, 31, v136
	v_lshl_add_u64 v[136:137], v[136:137], 1, s[6:7]
	global_store_short v[136:137], v139, off sc1
	v_or_b32_e32 v139, 0x600, v140
	v_add_u32_e32 v136, v139, v135
	v_ashrrev_i32_e32 v137, 31, v136
	v_cvt_pk_bf16_f32 v49, v49, s0
	v_lshl_add_u64 v[136:137], v[136:137], 1, s[6:7]
	v_add_u32_e32 v141, 0xc00, v140
	global_store_short v[136:137], v49, off sc1
	v_mul_f32_e32 v49, v50, v73
	v_add_u32_e32 v136, v141, v135
	v_mul_f32_e32 v49, v49, v134
	v_ashrrev_i32_e32 v137, 31, v136
	v_cvt_pk_bf16_f32 v49, v49, s0
	v_lshl_add_u64 v[136:137], v[136:137], 1, s[6:7]
	global_store_short v[136:137], v49, off sc1
	v_add_u32_e32 v136, 0x1200, v140
	v_mul_f32_e32 v49, v51, v72
	v_add_u32_e32 v50, v136, v135
	v_mul_f32_e32 v49, v49, v134
	v_ashrrev_i32_e32 v51, 31, v50
	v_cvt_pk_bf16_f32 v49, v49, s0
	v_lshl_add_u64 v[50:51], v[50:51], 1, s[6:7]
	global_store_short v[50:51], v49, off sc1
	v_mul_f32_e32 v49, v52, v122
	v_add_u32_e32 v52, 0x3000, v140
	v_add_u32_e32 v50, v52, v135
	v_mul_f32_e32 v49, v49, v134
	v_ashrrev_i32_e32 v51, 31, v50
	v_cvt_pk_bf16_f32 v49, v49, s0
	v_lshl_add_u64 v[50:51], v[50:51], 1, s[6:7]
	global_store_short v[50:51], v49, off sc1
	v_mul_f32_e32 v49, v53, v123
	v_add_u32_e32 v53, 0x3600, v140
	v_add_u32_e32 v50, v53, v135
	v_mul_f32_e32 v49, v49, v134
	v_ashrrev_i32_e32 v51, 31, v50
	v_cvt_pk_bf16_f32 v49, v49, s0
	v_lshl_add_u64 v[50:51], v[50:51], 1, s[6:7]
	global_store_short v[50:51], v49, off sc1
	v_mul_f32_e32 v49, v54, v124
	v_add_u32_e32 v54, 0x3c00, v140
	v_add_u32_e32 v50, v54, v135
	v_mul_f32_e32 v49, v49, v134
	v_ashrrev_i32_e32 v51, 31, v50
	v_cvt_pk_bf16_f32 v49, v49, s0
	v_lshl_add_u64 v[50:51], v[50:51], 1, s[6:7]
	global_store_short v[50:51], v49, off sc1
	v_mul_f32_e32 v49, v55, v126
	v_add_u32_e32 v55, 0x4200, v140
	v_add_u32_e32 v50, v55, v135
	v_mul_f32_e32 v49, v49, v134
	v_ashrrev_i32_e32 v51, 31, v50
	v_cvt_pk_bf16_f32 v49, v49, s0
	v_lshl_add_u64 v[50:51], v[50:51], 1, s[6:7]
	global_store_short v[50:51], v49, off sc1
	v_mul_f32_e32 v49, v56, v127
	v_add_u32_e32 v56, 0x6000, v140
	v_add_u32_e32 v50, v56, v135
	v_mul_f32_e32 v49, v49, v134
	v_ashrrev_i32_e32 v51, 31, v50
	v_cvt_pk_bf16_f32 v49, v49, s0
	v_lshl_add_u64 v[50:51], v[50:51], 1, s[6:7]
	global_store_short v[50:51], v49, off sc1
	v_mul_f32_e32 v49, v57, v125
	v_add_u32_e32 v57, 0x6600, v140
	v_add_u32_e32 v50, v57, v135
	v_mul_f32_e32 v49, v49, v134
	v_ashrrev_i32_e32 v51, 31, v50
	v_cvt_pk_bf16_f32 v49, v49, s0
	v_lshl_add_u64 v[50:51], v[50:51], 1, s[6:7]
	global_store_short v[50:51], v49, off sc1
	v_mul_f32_e32 v49, v58, v128
	v_add_u32_e32 v58, 0x6c00, v140
	v_add_u32_e32 v50, v58, v135
	v_mul_f32_e32 v49, v49, v134
	v_ashrrev_i32_e32 v51, 31, v50
	v_cvt_pk_bf16_f32 v49, v49, s0
	v_lshl_add_u64 v[50:51], v[50:51], 1, s[6:7]
	global_store_short v[50:51], v49, off sc1
	v_mul_f32_e32 v49, v59, v129
	v_add_u32_e32 v59, 0x7200, v140
	v_add_u32_e32 v50, v59, v135
	v_mul_f32_e32 v49, v49, v134
	v_ashrrev_i32_e32 v51, 31, v50
	v_cvt_pk_bf16_f32 v49, v49, s0
	v_lshl_add_u64 v[50:51], v[50:51], 1, s[6:7]
	global_store_short v[50:51], v49, off sc1
	v_mul_f32_e32 v49, v60, v132
	v_add_u32_e32 v60, 0x9000, v140
	v_add_u32_e32 v50, v60, v135
	v_mul_f32_e32 v49, v49, v134
	v_ashrrev_i32_e32 v51, 31, v50
	v_fmamk_f32 v131, v131, 0x3c000000, v119
	v_cvt_pk_bf16_f32 v49, v49, s0
	v_lshl_add_u64 v[50:51], v[50:51], 1, s[6:7]
	v_rsq_f32_e32 v131, v131
	global_store_short v[50:51], v49, off sc1
	v_mul_f32_e32 v49, v61, v133
	v_add_u32_e32 v61, 0x9600, v140
	v_add_u32_e32 v50, v61, v135
	v_mul_f32_e32 v49, v49, v134
	v_ashrrev_i32_e32 v51, 31, v50
	v_fmamk_f32 v130, v130, 0x3c000000, v119
	v_cvt_pk_bf16_f32 v49, v49, s0
	v_lshl_add_u64 v[50:51], v[50:51], 1, s[6:7]
	v_rsq_f32_e32 v130, v130
	global_store_short v[50:51], v49, off sc1
	v_mul_f32_e32 v49, v62, v131
	v_add_u32_e32 v62, 0x9c00, v140
	v_add_u32_e32 v50, v62, v135
	v_mul_f32_e32 v49, v134, v49
	v_ashrrev_i32_e32 v51, 31, v50
	v_cvt_pk_bf16_f32 v49, v49, s0
	v_lshl_add_u64 v[50:51], v[50:51], 1, s[6:7]
	global_store_short v[50:51], v49, off sc1
	v_mul_f32_e32 v49, v63, v130
	v_add_u32_e32 v63, 0xa200, v140
	v_add_u32_e32 v50, v63, v135
	v_mul_f32_e32 v49, v134, v49
	v_ashrrev_i32_e32 v51, 31, v50
	v_cvt_pk_bf16_f32 v49, v49, s0
	v_lshl_add_u64 v[50:51], v[50:51], 1, s[6:7]
	global_store_short v[50:51], v49, off sc1
	v_or_b32_e32 v49, s72, v65
	v_add_u32_e32 v50, v140, v49
	s_waitcnt vmcnt(18)
	v_mul_f32_e32 v32, v32, v48
	v_ashrrev_i32_e32 v51, 31, v50
	v_cvt_pk_bf16_f32 v32, v32, s0
	v_lshl_add_u64 v[50:51], v[50:51], 1, s[6:7]
	global_store_short v[50:51], v32, off sc1
	v_mul_f32_e32 v32, v33, v70
	v_mul_f32_e32 v32, v32, v48
	v_cvt_pk_bf16_f32 v50, v32, s0
	v_add_u32_e32 v32, v139, v49
	v_ashrrev_i32_e32 v33, 31, v32
	v_lshl_add_u64 v[32:33], v[32:33], 1, s[6:7]
	global_store_short v[32:33], v50, off sc1
	v_mul_f32_e32 v32, v34, v73
	v_mul_f32_e32 v32, v32, v48
	v_cvt_pk_bf16_f32 v34, v32, s0
	v_add_u32_e32 v32, v141, v49
	v_ashrrev_i32_e32 v33, 31, v32
	v_lshl_add_u64 v[32:33], v[32:33], 1, s[6:7]
	global_store_short v[32:33], v34, off sc1
	v_mul_f32_e32 v32, v35, v72
	v_mul_f32_e32 v32, v32, v48
	v_cvt_pk_bf16_f32 v34, v32, s0
	v_add_u32_e32 v32, v136, v49
	v_ashrrev_i32_e32 v33, 31, v32
	v_lshl_add_u64 v[32:33], v[32:33], 1, s[6:7]
	global_store_short v[32:33], v34, off sc1
	v_mul_f32_e32 v32, v36, v122
	v_mul_f32_e32 v32, v32, v48
	v_cvt_pk_bf16_f32 v34, v32, s0
	v_add_u32_e32 v32, v52, v49
	v_ashrrev_i32_e32 v33, 31, v32
	v_lshl_add_u64 v[32:33], v[32:33], 1, s[6:7]
	global_store_short v[32:33], v34, off sc1
	v_mul_f32_e32 v32, v37, v123
	v_mul_f32_e32 v32, v32, v48
	v_cvt_pk_bf16_f32 v34, v32, s0
	v_add_u32_e32 v32, v53, v49
	v_ashrrev_i32_e32 v33, 31, v32
	v_lshl_add_u64 v[32:33], v[32:33], 1, s[6:7]
	global_store_short v[32:33], v34, off sc1
	v_mul_f32_e32 v32, v38, v124
	v_mul_f32_e32 v32, v32, v48
	v_cvt_pk_bf16_f32 v34, v32, s0
	v_add_u32_e32 v32, v54, v49
	v_ashrrev_i32_e32 v33, 31, v32
	v_lshl_add_u64 v[32:33], v[32:33], 1, s[6:7]
	global_store_short v[32:33], v34, off sc1
	v_mul_f32_e32 v32, v39, v126
	v_mul_f32_e32 v32, v32, v48
	v_cvt_pk_bf16_f32 v34, v32, s0
	v_add_u32_e32 v32, v55, v49
	v_ashrrev_i32_e32 v33, 31, v32
	v_lshl_add_u64 v[32:33], v[32:33], 1, s[6:7]
	global_store_short v[32:33], v34, off sc1
	v_mul_f32_e32 v32, v40, v127
	v_mul_f32_e32 v32, v32, v48
	v_cvt_pk_bf16_f32 v34, v32, s0
	v_add_u32_e32 v32, v56, v49
	v_ashrrev_i32_e32 v33, 31, v32
	v_lshl_add_u64 v[32:33], v[32:33], 1, s[6:7]
	global_store_short v[32:33], v34, off sc1
	v_mul_f32_e32 v32, v41, v125
	v_mul_f32_e32 v32, v32, v48
	v_cvt_pk_bf16_f32 v34, v32, s0
	v_add_u32_e32 v32, v57, v49
	v_ashrrev_i32_e32 v33, 31, v32
	v_lshl_add_u64 v[32:33], v[32:33], 1, s[6:7]
	global_store_short v[32:33], v34, off sc1
	v_mul_f32_e32 v32, v42, v128
	v_mul_f32_e32 v32, v32, v48
	v_cvt_pk_bf16_f32 v34, v32, s0
	v_add_u32_e32 v32, v58, v49
	v_ashrrev_i32_e32 v33, 31, v32
	v_lshl_add_u64 v[32:33], v[32:33], 1, s[6:7]
	global_store_short v[32:33], v34, off sc1
	v_mul_f32_e32 v32, v43, v129
	v_mul_f32_e32 v32, v32, v48
	v_cvt_pk_bf16_f32 v34, v32, s0
	v_add_u32_e32 v32, v59, v49
	v_ashrrev_i32_e32 v33, 31, v32
	v_lshl_add_u64 v[32:33], v[32:33], 1, s[6:7]
	global_store_short v[32:33], v34, off sc1
	v_mul_f32_e32 v32, v44, v132
	v_mul_f32_e32 v32, v32, v48
	v_cvt_pk_bf16_f32 v34, v32, s0
	v_add_u32_e32 v32, v60, v49
	v_ashrrev_i32_e32 v33, 31, v32
	v_lshl_add_u64 v[32:33], v[32:33], 1, s[6:7]
	global_store_short v[32:33], v34, off sc1
	v_mul_f32_e32 v32, v45, v133
	v_mul_f32_e32 v32, v32, v48
	v_cvt_pk_bf16_f32 v34, v32, s0
	v_add_u32_e32 v32, v61, v49
	v_ashrrev_i32_e32 v33, 31, v32
	v_lshl_add_u64 v[32:33], v[32:33], 1, s[6:7]
	global_store_short v[32:33], v34, off sc1
	v_mul_f32_e32 v32, v46, v131
	v_mul_f32_e32 v32, v32, v48
	v_cvt_pk_bf16_f32 v34, v32, s0
	v_add_u32_e32 v32, v62, v49
	v_ashrrev_i32_e32 v33, 31, v32
	v_lshl_add_u64 v[32:33], v[32:33], 1, s[6:7]
	global_store_short v[32:33], v34, off sc1
	v_mul_f32_e32 v32, v47, v130
	v_mul_f32_e32 v32, v32, v48
	v_cvt_pk_bf16_f32 v34, v32, s0
	v_add_u32_e32 v32, v63, v49
	v_ashrrev_i32_e32 v33, 31, v32
	v_lshl_add_u64 v[32:33], v[32:33], 1, s[6:7]
	global_store_short v[32:33], v34, off sc1
	v_add_u32_e32 v34, s72, v74
	v_add_u32_e32 v32, v140, v34
	s_waitcnt vmcnt(33)
	v_mul_f32_e32 v16, v16, v138
	v_ashrrev_i32_e32 v33, 31, v32
	v_cvt_pk_bf16_f32 v16, v16, s0
	v_lshl_add_u64 v[32:33], v[32:33], 1, s[6:7]
	global_store_short v[32:33], v16, off sc1
	v_mul_f32_e32 v16, v17, v70
	v_mul_f32_e32 v16, v16, v138
	v_cvt_pk_bf16_f32 v32, v16, s0
	v_add_u32_e32 v16, v139, v34
	v_ashrrev_i32_e32 v17, 31, v16
	v_lshl_add_u64 v[16:17], v[16:17], 1, s[6:7]
	global_store_short v[16:17], v32, off sc1
	v_mul_f32_e32 v16, v18, v73
	v_mul_f32_e32 v16, v16, v138
	v_cvt_pk_bf16_f32 v18, v16, s0
	v_add_u32_e32 v16, v141, v34
	v_ashrrev_i32_e32 v17, 31, v16
	v_lshl_add_u64 v[16:17], v[16:17], 1, s[6:7]
	global_store_short v[16:17], v18, off sc1
	v_mul_f32_e32 v16, v19, v72
	v_mul_f32_e32 v16, v16, v138
	v_cvt_pk_bf16_f32 v18, v16, s0
	v_add_u32_e32 v16, v136, v34
	v_ashrrev_i32_e32 v17, 31, v16
	v_lshl_add_u64 v[16:17], v[16:17], 1, s[6:7]
	global_store_short v[16:17], v18, off sc1
	v_mul_f32_e32 v16, v20, v122
	v_mul_f32_e32 v16, v16, v138
	v_cvt_pk_bf16_f32 v18, v16, s0
	v_add_u32_e32 v16, v52, v34
	v_ashrrev_i32_e32 v17, 31, v16
	v_lshl_add_u64 v[16:17], v[16:17], 1, s[6:7]
	global_store_short v[16:17], v18, off sc1
	v_mul_f32_e32 v16, v21, v123
	v_mul_f32_e32 v16, v16, v138
	v_cvt_pk_bf16_f32 v18, v16, s0
	v_add_u32_e32 v16, v53, v34
	v_ashrrev_i32_e32 v17, 31, v16
	v_lshl_add_u64 v[16:17], v[16:17], 1, s[6:7]
	global_store_short v[16:17], v18, off sc1
	v_mul_f32_e32 v16, v22, v124
	v_mul_f32_e32 v16, v16, v138
	v_cvt_pk_bf16_f32 v18, v16, s0
	v_add_u32_e32 v16, v54, v34
	v_ashrrev_i32_e32 v17, 31, v16
	v_lshl_add_u64 v[16:17], v[16:17], 1, s[6:7]
	global_store_short v[16:17], v18, off sc1
	v_mul_f32_e32 v16, v23, v126
	v_mul_f32_e32 v16, v16, v138
	v_cvt_pk_bf16_f32 v18, v16, s0
	v_add_u32_e32 v16, v55, v34
	v_ashrrev_i32_e32 v17, 31, v16
	v_lshl_add_u64 v[16:17], v[16:17], 1, s[6:7]
	global_store_short v[16:17], v18, off sc1
	v_mul_f32_e32 v16, v24, v127
	v_mul_f32_e32 v16, v16, v138
	v_cvt_pk_bf16_f32 v18, v16, s0
	v_add_u32_e32 v16, v56, v34
	v_ashrrev_i32_e32 v17, 31, v16
	v_lshl_add_u64 v[16:17], v[16:17], 1, s[6:7]
	global_store_short v[16:17], v18, off sc1
	v_mul_f32_e32 v16, v25, v125
	v_mul_f32_e32 v16, v16, v138
	v_cvt_pk_bf16_f32 v18, v16, s0
	v_add_u32_e32 v16, v57, v34
	v_ashrrev_i32_e32 v17, 31, v16
	v_lshl_add_u64 v[16:17], v[16:17], 1, s[6:7]
	global_store_short v[16:17], v18, off sc1
	v_mul_f32_e32 v16, v26, v128
	v_mul_f32_e32 v16, v16, v138
	v_cvt_pk_bf16_f32 v18, v16, s0
	v_add_u32_e32 v16, v58, v34
	v_ashrrev_i32_e32 v17, 31, v16
	v_lshl_add_u64 v[16:17], v[16:17], 1, s[6:7]
	global_store_short v[16:17], v18, off sc1
	v_mul_f32_e32 v16, v27, v129
	v_mul_f32_e32 v16, v16, v138
	v_cvt_pk_bf16_f32 v18, v16, s0
	v_add_u32_e32 v16, v59, v34
	v_ashrrev_i32_e32 v17, 31, v16
	v_lshl_add_u64 v[16:17], v[16:17], 1, s[6:7]
	global_store_short v[16:17], v18, off sc1
	v_mul_f32_e32 v16, v28, v132
	v_mul_f32_e32 v16, v16, v138
	v_cvt_pk_bf16_f32 v18, v16, s0
	v_add_u32_e32 v16, v60, v34
	v_ashrrev_i32_e32 v17, 31, v16
	v_lshl_add_u64 v[16:17], v[16:17], 1, s[6:7]
	global_store_short v[16:17], v18, off sc1
	v_mul_f32_e32 v16, v29, v133
	v_mul_f32_e32 v16, v16, v138
	v_cvt_pk_bf16_f32 v18, v16, s0
	v_add_u32_e32 v16, v61, v34
	v_ashrrev_i32_e32 v17, 31, v16
	v_lshl_add_u64 v[16:17], v[16:17], 1, s[6:7]
	global_store_short v[16:17], v18, off sc1
	v_mul_f32_e32 v16, v30, v131
	v_mul_f32_e32 v16, v16, v138
	v_cvt_pk_bf16_f32 v18, v16, s0
	v_add_u32_e32 v16, v62, v34
	v_ashrrev_i32_e32 v17, 31, v16
	v_lshl_add_u64 v[16:17], v[16:17], 1, s[6:7]
	global_store_short v[16:17], v18, off sc1
	v_mul_f32_e32 v16, v31, v130
	v_mul_f32_e32 v16, v16, v138
	v_cvt_pk_bf16_f32 v18, v16, s0
	v_add_u32_e32 v16, v63, v34
	v_ashrrev_i32_e32 v17, 31, v16
	v_lshl_add_u64 v[16:17], v[16:17], 1, s[6:7]
	global_store_short v[16:17], v18, off sc1
	v_add_u32_e32 v18, s72, v98
	v_add_u32_e32 v16, v140, v18
	s_waitcnt vmcnt(48)
	v_mul_f32_e32 v0, v0, v121
	v_ashrrev_i32_e32 v17, 31, v16
	v_cvt_pk_bf16_f32 v0, v0, s0
	v_lshl_add_u64 v[16:17], v[16:17], 1, s[6:7]
	global_store_short v[16:17], v0, off sc1
	v_mul_f32_e32 v0, v1, v70
	v_mul_f32_e32 v0, v0, v121
	v_cvt_pk_bf16_f32 v16, v0, s0
	v_add_u32_e32 v0, v139, v18
	v_ashrrev_i32_e32 v1, 31, v0
	v_lshl_add_u64 v[0:1], v[0:1], 1, s[6:7]
	global_store_short v[0:1], v16, off sc1
	v_mul_f32_e32 v0, v2, v73
	v_mul_f32_e32 v0, v0, v121
	v_cvt_pk_bf16_f32 v2, v0, s0
	v_add_u32_e32 v0, v141, v18
	v_ashrrev_i32_e32 v1, 31, v0
	v_lshl_add_u64 v[0:1], v[0:1], 1, s[6:7]
	global_store_short v[0:1], v2, off sc1
	v_mul_f32_e32 v0, v3, v72
	v_mul_f32_e32 v0, v0, v121
	v_cvt_pk_bf16_f32 v2, v0, s0
	v_add_u32_e32 v0, v136, v18
	v_ashrrev_i32_e32 v1, 31, v0
	v_lshl_add_u64 v[0:1], v[0:1], 1, s[6:7]
	global_store_short v[0:1], v2, off sc1
	v_mul_f32_e32 v0, v4, v122
	v_mul_f32_e32 v0, v0, v121
	v_cvt_pk_bf16_f32 v2, v0, s0
	v_add_u32_e32 v0, v52, v18
	v_ashrrev_i32_e32 v1, 31, v0
	v_lshl_add_u64 v[0:1], v[0:1], 1, s[6:7]
	global_store_short v[0:1], v2, off sc1
	v_mul_f32_e32 v0, v5, v123
	v_mul_f32_e32 v0, v0, v121
	v_cvt_pk_bf16_f32 v2, v0, s0
	v_add_u32_e32 v0, v53, v18
	v_ashrrev_i32_e32 v1, 31, v0
	v_lshl_add_u64 v[0:1], v[0:1], 1, s[6:7]
	global_store_short v[0:1], v2, off sc1
	v_mul_f32_e32 v0, v6, v124
	v_mul_f32_e32 v0, v0, v121
	v_cvt_pk_bf16_f32 v2, v0, s0
	v_add_u32_e32 v0, v54, v18
	v_ashrrev_i32_e32 v1, 31, v0
	v_lshl_add_u64 v[0:1], v[0:1], 1, s[6:7]
	global_store_short v[0:1], v2, off sc1
	v_mul_f32_e32 v0, v7, v126
	v_mul_f32_e32 v0, v0, v121
	v_cvt_pk_bf16_f32 v2, v0, s0
	v_add_u32_e32 v0, v55, v18
	v_ashrrev_i32_e32 v1, 31, v0
	v_lshl_add_u64 v[0:1], v[0:1], 1, s[6:7]
	global_store_short v[0:1], v2, off sc1
	v_mul_f32_e32 v0, v8, v127
	v_mul_f32_e32 v0, v0, v121
	v_cvt_pk_bf16_f32 v2, v0, s0
	v_add_u32_e32 v0, v56, v18
	v_ashrrev_i32_e32 v1, 31, v0
	v_lshl_add_u64 v[0:1], v[0:1], 1, s[6:7]
	global_store_short v[0:1], v2, off sc1
	v_mul_f32_e32 v0, v9, v125
	v_mul_f32_e32 v0, v0, v121
	v_cvt_pk_bf16_f32 v2, v0, s0
	v_add_u32_e32 v0, v57, v18
	v_ashrrev_i32_e32 v1, 31, v0
	v_lshl_add_u64 v[0:1], v[0:1], 1, s[6:7]
	global_store_short v[0:1], v2, off sc1
	v_mul_f32_e32 v0, v10, v128
	v_mul_f32_e32 v0, v0, v121
	v_cvt_pk_bf16_f32 v2, v0, s0
	v_add_u32_e32 v0, v58, v18
	v_ashrrev_i32_e32 v1, 31, v0
	v_lshl_add_u64 v[0:1], v[0:1], 1, s[6:7]
	global_store_short v[0:1], v2, off sc1
	v_mul_f32_e32 v0, v11, v129
	v_mul_f32_e32 v0, v0, v121
	v_cvt_pk_bf16_f32 v2, v0, s0
	v_add_u32_e32 v0, v59, v18
	v_ashrrev_i32_e32 v1, 31, v0
	v_lshl_add_u64 v[0:1], v[0:1], 1, s[6:7]
	global_store_short v[0:1], v2, off sc1
	v_mul_f32_e32 v0, v12, v132
	v_mul_f32_e32 v0, v0, v121
	v_cvt_pk_bf16_f32 v2, v0, s0
	v_add_u32_e32 v0, v60, v18
	v_ashrrev_i32_e32 v1, 31, v0
	v_lshl_add_u64 v[0:1], v[0:1], 1, s[6:7]
	global_store_short v[0:1], v2, off sc1
	v_mul_f32_e32 v0, v13, v133
	v_mul_f32_e32 v0, v0, v121
	v_cvt_pk_bf16_f32 v2, v0, s0
	v_add_u32_e32 v0, v61, v18
	v_ashrrev_i32_e32 v1, 31, v0
	v_lshl_add_u64 v[0:1], v[0:1], 1, s[6:7]
	global_store_short v[0:1], v2, off sc1
	v_mul_f32_e32 v0, v14, v131
	v_mul_f32_e32 v0, v0, v121
	v_cvt_pk_bf16_f32 v2, v0, s0
	v_add_u32_e32 v0, v62, v18
	v_ashrrev_i32_e32 v1, 31, v0
	v_lshl_add_u64 v[0:1], v[0:1], 1, s[6:7]
	global_store_short v[0:1], v2, off sc1
	v_mul_f32_e32 v0, v15, v130
	v_mul_f32_e32 v70, v0, v121
	v_add_u32_e32 v72, v63, v18
	s_branch .LBB0_575

.LBB0_652:
	s_lshl_b32 s50, s69, 18
	s_lshl_b32 s51, s49, 15
	s_add_i32 s50, s50, s51
	s_lshl_b32 s51, s69, 10
	s_lshl_b32 s68, s49, 7
	s_add_i32 s51, s51, s68
	v_or_b32_e32 v71, s51, v64
	v_mul_lo_u32 v71, v71, s62
	v_or_b32_e32 v70, s50, v73
	v_add_u32_e32 v71, 0x800000, v71
	v_add_u32_e32 v108, s70, v72
	v_cndmask_b32_e64 v109, v70, v71, s[0:1]
	v_add_u32_e32 v70, v109, v108
	v_ashrrev_i32_e32 v71, 31, v70
	v_cvt_pk_bf16_f32 v106, v48, v49
	v_cvt_pk_bf16_f32 v107, v50, v51
	v_lshl_add_u64 v[70:71], v[70:71], 1, s[6:7]
	v_add_u32_e32 v110, 8, v108
	global_store_dwordx2 v[70:71], v[106:107], off sc1
	v_add_u32_e32 v70, v109, v110
	v_ashrrev_i32_e32 v71, 31, v70
	v_cvt_pk_bf16_f32 v106, v52, v53
	v_cvt_pk_bf16_f32 v107, v54, v55
	v_lshl_add_u64 v[70:71], v[70:71], 1, s[6:7]
	v_add_u32_e32 v111, 16, v108
	global_store_dwordx2 v[70:71], v[106:107], off sc1
	v_add_u32_e32 v70, v109, v111
	v_ashrrev_i32_e32 v71, 31, v70
	v_cvt_pk_bf16_f32 v106, v56, v57
	v_cvt_pk_bf16_f32 v107, v58, v59
	v_lshl_add_u64 v[70:71], v[70:71], 1, s[6:7]
	v_add_u32_e32 v112, 24, v108
	global_store_dwordx2 v[70:71], v[106:107], off sc1
	v_add_u32_e32 v70, v109, v112
	v_ashrrev_i32_e32 v71, 31, v70
	v_cvt_pk_bf16_f32 v106, v60, v61
	v_cvt_pk_bf16_f32 v107, v62, v63
	v_lshl_add_u64 v[70:71], v[70:71], 1, s[6:7]
	global_store_dwordx2 v[70:71], v[106:107], off sc1
	v_or_b32_e32 v71, s51, v65
	v_mul_lo_u32 v71, v71, s62
	v_or_b32_e32 v70, s50, v76
	v_add_u32_e32 v71, 0x800000, v71
	v_cndmask_b32_e64 v109, v70, v71, s[0:1]
	v_add_u32_e32 v70, v109, v108
	v_ashrrev_i32_e32 v71, 31, v70
	v_cvt_pk_bf16_f32 v106, v32, v33
	v_cvt_pk_bf16_f32 v107, v34, v35
	v_lshl_add_u64 v[70:71], v[70:71], 1, s[6:7]
	global_store_dwordx2 v[70:71], v[106:107], off sc1
	v_add_u32_e32 v70, v109, v110
	v_ashrrev_i32_e32 v71, 31, v70
	v_cvt_pk_bf16_f32 v106, v36, v37
	v_cvt_pk_bf16_f32 v107, v38, v39
	v_lshl_add_u64 v[70:71], v[70:71], 1, s[6:7]
	global_store_dwordx2 v[70:71], v[106:107], off sc1
	v_add_u32_e32 v70, v109, v111
	v_ashrrev_i32_e32 v71, 31, v70
	v_cvt_pk_bf16_f32 v106, v40, v41
	v_cvt_pk_bf16_f32 v107, v42, v43
	v_lshl_add_u64 v[70:71], v[70:71], 1, s[6:7]
	global_store_dwordx2 v[70:71], v[106:107], off sc1
	v_add_u32_e32 v70, v109, v112
	v_ashrrev_i32_e32 v71, 31, v70
	v_cvt_pk_bf16_f32 v106, v44, v45
	v_cvt_pk_bf16_f32 v107, v46, v47
	v_lshl_add_u64 v[70:71], v[70:71], 1, s[6:7]
	global_store_dwordx2 v[70:71], v[106:107], off sc1
	v_or_b32_e32 v71, s51, v74
	v_mul_lo_u32 v71, v71, s62
	v_or_b32_e32 v70, s50, v77
	v_add_u32_e32 v71, 0x800000, v71
	v_cndmask_b32_e64 v109, v70, v71, s[0:1]
	v_add_u32_e32 v70, v109, v108
	v_ashrrev_i32_e32 v71, 31, v70
	v_cvt_pk_bf16_f32 v106, v16, v17
	v_cvt_pk_bf16_f32 v107, v18, v19
	v_lshl_add_u64 v[70:71], v[70:71], 1, s[6:7]
	global_store_dwordx2 v[70:71], v[106:107], off sc1
	v_add_u32_e32 v70, v109, v110
	v_ashrrev_i32_e32 v71, 31, v70
	v_cvt_pk_bf16_f32 v106, v20, v21
	v_cvt_pk_bf16_f32 v107, v22, v23
	v_lshl_add_u64 v[70:71], v[70:71], 1, s[6:7]
	global_store_dwordx2 v[70:71], v[106:107], off sc1
	v_add_u32_e32 v70, v109, v111
	v_ashrrev_i32_e32 v71, 31, v70
	v_cvt_pk_bf16_f32 v106, v24, v25
	v_cvt_pk_bf16_f32 v107, v26, v27
	v_lshl_add_u64 v[70:71], v[70:71], 1, s[6:7]
	global_store_dwordx2 v[70:71], v[106:107], off sc1
	v_add_u32_e32 v70, v109, v112
	v_ashrrev_i32_e32 v71, 31, v70
	v_cvt_pk_bf16_f32 v106, v28, v29
	v_cvt_pk_bf16_f32 v107, v30, v31
	v_lshl_add_u64 v[70:71], v[70:71], 1, s[6:7]
	global_store_dwordx2 v[70:71], v[106:107], off sc1
	v_or_b32_e32 v71, s51, v78
	v_mul_lo_u32 v71, v71, s62
	v_or_b32_e32 v70, s50, v79
	v_add_u32_e32 v71, 0x800000, v71
	v_cndmask_b32_e64 v109, v70, v71, s[0:1]
	v_add_u32_e32 v70, v109, v108
	v_ashrrev_i32_e32 v71, 31, v70
	v_cvt_pk_bf16_f32 v106, v0, v1
	v_cvt_pk_bf16_f32 v107, v2, v3
	v_lshl_add_u64 v[70:71], v[70:71], 1, s[6:7]
	global_store_dwordx2 v[70:71], v[106:107], off sc1
	v_add_u32_e32 v70, v109, v110
	v_ashrrev_i32_e32 v71, 31, v70
	v_cvt_pk_bf16_f32 v106, v4, v5
	v_cvt_pk_bf16_f32 v107, v6, v7
	v_lshl_add_u64 v[70:71], v[70:71], 1, s[6:7]
	global_store_dwordx2 v[70:71], v[106:107], off sc1
	v_add_u32_e32 v70, v109, v111
	v_ashrrev_i32_e32 v71, 31, v70
	v_cvt_pk_bf16_f32 v106, v8, v9
	v_cvt_pk_bf16_f32 v107, v10, v11
	v_lshl_add_u64 v[70:71], v[70:71], 1, s[6:7]
	global_store_dwordx2 v[70:71], v[106:107], off sc1
	v_add_u32_e32 v70, v109, v112
	v_ashrrev_i32_e32 v71, 31, v70
	v_cvt_pk_bf16_f32 v106, v12, v13
	v_cvt_pk_bf16_f32 v107, v14, v15
	v_lshl_add_u64 v[70:71], v[70:71], 1, s[6:7]
	global_store_dwordx2 v[70:71], v[106:107], off sc1
	s_branch .LBB0_646
.LBB0_653:
	s_and_b64 vcc, exec, s[0:1]
	s_cbranch_vccz .LBB0_646
	v_mov_b32_e32 v70, s63
	ds_read_b64 v[70:71], v70
	v_xor_b32_e32 v110, 2, v105
	v_add_u32_e32 v114, s48, v72
	v_xor_b32_e32 v111, 4, v105
	v_mul_f32_e32 v115, v32, v32
	s_waitcnt lgkmcnt(0)
	v_readfirstlane_b32 s0, v70
	v_readfirstlane_b32 s1, v71
	s_nop 4
	global_load_dword v109, v103, s[0:1] offset:768
	global_load_dword v108, v103, s[0:1] offset:896
	global_load_dword v107, v103, s[0:1] offset:1024
	global_load_dword v106, v103, s[0:1] offset:1152
	v_and_b32_e32 v70, 64, v105
	v_xor_b32_e32 v71, 1, v105
	v_add_u32_e32 v116, 64, v70
	v_cmp_lt_i32_e32 vcc, v71, v116
	v_mul_lo_u32 v70, v114, s64
	v_xor_b32_e32 v112, 8, v105
	v_cndmask_b32_e32 v114, v105, v71, vcc
	v_cmp_lt_i32_e32 vcc, v110, v116
	v_fmac_f32_e32 v115, v48, v48
	v_fmac_f32_e32 v115, v16, v16
	v_cndmask_b32_e32 v110, v105, v110, vcc
	v_cmp_lt_i32_e32 vcc, v111, v116
	v_fmac_f32_e32 v115, v0, v0
	v_xor_b32_e32 v113, 16, v105
	v_cndmask_b32_e32 v111, v105, v111, vcc
	v_cmp_lt_i32_e32 vcc, v112, v116
	v_mul_f32_e32 v118, v33, v33
	v_fmac_f32_e32 v118, v49, v49
	v_cndmask_b32_e32 v120, v105, v112, vcc
	v_lshlrev_b32_e32 v112, 2, v114
	ds_bpermute_b32 v114, v112, v115
	v_cmp_lt_i32_e32 vcc, v113, v116
	v_fmac_f32_e32 v118, v17, v17
	v_fmac_f32_e32 v118, v1, v1
	v_cndmask_b32_e32 v121, v105, v113, vcc
	v_lshlrev_b32_e32 v113, 2, v110
	s_waitcnt lgkmcnt(0)
	v_add_f32_e32 v110, v115, v114
	ds_bpermute_b32 v115, v113, v110
	v_lshlrev_b32_e32 v114, 2, v111
	ds_bpermute_b32 v122, v112, v118
	v_lshlrev_b32_e32 v111, 2, v120
	v_mul_f32_e32 v119, v34, v34
	s_waitcnt lgkmcnt(1)
	v_add_f32_e32 v115, v110, v115
	ds_bpermute_b32 v123, v114, v115
	v_lshlrev_b32_e32 v110, 2, v121
	s_waitcnt lgkmcnt(1)
	v_add_f32_e32 v118, v118, v122
	ds_bpermute_b32 v122, v113, v118
	v_fmac_f32_e32 v119, v50, v50
	s_waitcnt lgkmcnt(1)
	v_add_f32_e32 v115, v115, v123
	ds_bpermute_b32 v121, v111, v115
	v_fmac_f32_e32 v119, v18, v18
	s_waitcnt lgkmcnt(1)
	v_add_f32_e32 v118, v118, v122
	ds_bpermute_b32 v120, v114, v118
	v_fmac_f32_e32 v119, v2, v2
	s_waitcnt lgkmcnt(1)
	v_add_f32_e32 v115, v115, v121
	ds_bpermute_b32 v121, v110, v115
	ds_bpermute_b32 v122, v112, v119
	s_waitcnt lgkmcnt(2)
	v_add_f32_e32 v118, v118, v120
	ds_bpermute_b32 v120, v111, v118
	s_mul_i32 s0, s49, 0xc0
	s_waitcnt lgkmcnt(2)
	v_add_f32_e32 v115, v115, v121
	v_fmamk_f32 v115, v115, 0x3c000000, v104
	v_rsq_f32_e32 v115, v115
	s_ashr_i32 s1, s0, 31
	v_lshl_add_u64 v[116:117], s[0:1], 1, v[68:69]
	v_ashrrev_i32_e32 v71, 31, v70
	v_mul_f32_e32 v48, v48, v115
	v_mul_f32_e32 v16, v16, v115
	v_mul_f32_e32 v32, v32, v115
	v_lshl_add_u64 v[70:71], v[70:71], 1, v[116:117]
	s_waitcnt lgkmcnt(0)
	v_add_f32_e32 v116, v118, v120
	v_add_f32_e32 v118, v119, v122
	ds_bpermute_b32 v117, v110, v116
	v_mul_f32_e32 v0, v0, v115
	s_waitcnt lgkmcnt(0)
	v_add_f32_e32 v116, v116, v117
	v_fmamk_f32 v116, v116, 0x3c000000, v104
	v_rsq_f32_e32 v116, v116
	s_waitcnt vmcnt(3)
	v_mul_f32_e32 v48, v109, v48
	s_waitcnt vmcnt(2)
	v_mul_f32_e32 v32, v108, v32
	s_waitcnt vmcnt(1)
	v_mul_f32_e32 v16, v107, v16
	v_cvt_pk_bf16_f32 v48, v48, s0
	v_cvt_pk_bf16_f32 v16, v16, s0
	v_cvt_pk_bf16_f32 v32, v32, s0
	global_store_short v[70:71], v48, off sc1
	global_store_short v[70:71], v32, off offset:64 sc1
	global_store_short v[70:71], v16, off offset:128 sc1
	ds_bpermute_b32 v16, v113, v118
	s_waitcnt vmcnt(3)
	v_mul_f32_e32 v0, v106, v0
	v_cvt_pk_bf16_f32 v0, v0, s0
	global_store_short v[70:71], v0, off offset:192 sc1
	v_mul_f32_e32 v0, v49, v116
	s_waitcnt lgkmcnt(0)
	v_add_f32_e32 v16, v118, v16
	ds_bpermute_b32 v32, v114, v16
	v_mul_f32_e32 v0, v109, v0
	v_cvt_pk_bf16_f32 v0, v0, s0
	global_store_short v[70:71], v0, off offset:3072 sc1
	v_mul_f32_e32 v0, v33, v116
	s_waitcnt lgkmcnt(0)
	v_add_f32_e32 v16, v16, v32
	ds_bpermute_b32 v32, v111, v16
	v_mul_f32_e32 v0, v108, v0
	v_cvt_pk_bf16_f32 v0, v0, s0
	global_store_short v[70:71], v0, off offset:3136 sc1
	v_mul_f32_e32 v0, v17, v116
	s_waitcnt lgkmcnt(0)
	v_add_f32_e32 v16, v16, v32
	ds_bpermute_b32 v17, v110, v16
	v_mul_f32_e32 v0, v107, v0
	v_cvt_pk_bf16_f32 v0, v0, s0
	global_store_short v[70:71], v0, off offset:3200 sc1
	v_mul_f32_e32 v0, v1, v116
	s_waitcnt lgkmcnt(0)
	v_add_f32_e32 v1, v16, v17
	v_fmamk_f32 v1, v1, 0x3c000000, v104
	v_rsq_f32_e32 v16, v1
	v_mul_f32_e32 v1, v35, v35
	v_fmac_f32_e32 v1, v51, v51
	v_fmac_f32_e32 v1, v19, v19
	v_fmac_f32_e32 v1, v3, v3
	ds_bpermute_b32 v17, v112, v1
	v_mul_f32_e32 v0, v106, v0
	v_cvt_pk_bf16_f32 v0, v0, s0
	global_store_short v[70:71], v0, off offset:3264 sc1
	v_mul_f32_e32 v0, v50, v16
	s_waitcnt lgkmcnt(0)
	v_add_f32_e32 v17, v1, v17
	ds_bpermute_b32 v33, v113, v17
	v_mul_f32_e32 v0, v109, v0
	v_cvt_pk_bf16_f32 v32, v0, s0
	v_add_co_u32_e32 v0, vcc, s54, v70
	s_waitcnt lgkmcnt(0)
	v_add_f32_e32 v17, v17, v33
	ds_bpermute_b32 v33, v114, v17
	v_addc_co_u32_e32 v1, vcc, 0, v71, vcc
	global_store_short v[0:1], v32, off offset:2048 sc1
	v_mul_f32_e32 v32, v34, v16
	s_waitcnt lgkmcnt(0)
	v_add_f32_e32 v17, v17, v33
	ds_bpermute_b32 v33, v111, v17
	v_mul_f32_e32 v32, v108, v32
	v_cvt_pk_bf16_f32 v32, v32, s0
	global_store_short v[0:1], v32, off offset:2112 sc1
	v_mul_f32_e32 v18, v18, v16
	s_waitcnt lgkmcnt(0)
	v_add_f32_e32 v17, v17, v33
	ds_bpermute_b32 v32, v110, v17
	v_mul_f32_e32 v2, v2, v16
	v_mul_f32_e32 v18, v107, v18
	v_cvt_pk_bf16_f32 v18, v18, s0
	global_store_short v[0:1], v18, off offset:2176 sc1
	s_waitcnt lgkmcnt(0)
	v_add_f32_e32 v16, v17, v32
	v_mul_f32_e32 v17, v36, v36
	v_fmac_f32_e32 v17, v52, v52
	v_fmac_f32_e32 v17, v20, v20
	v_fmac_f32_e32 v17, v4, v4
	ds_bpermute_b32 v18, v112, v17
	v_fmamk_f32 v16, v16, 0x3c000000, v104
	v_rsq_f32_e32 v16, v16
	v_mul_f32_e32 v2, v106, v2
	v_cvt_pk_bf16_f32 v2, v2, s0
	s_waitcnt lgkmcnt(0)
	v_add_f32_e32 v17, v17, v18
	ds_bpermute_b32 v18, v113, v17
	global_store_short v[0:1], v2, off offset:2240 sc1
	v_mul_f32_e32 v0, v51, v16
	v_mul_f32_e32 v0, v109, v0
	v_cvt_pk_bf16_f32 v2, v0, s0
	s_waitcnt lgkmcnt(0)
	v_add_f32_e32 v17, v17, v18
	ds_bpermute_b32 v18, v114, v17
	v_add_co_u32_e32 v0, vcc, s55, v70
	s_waitcnt lgkmcnt(0)
	v_add_f32_e32 v17, v17, v18
	v_addc_co_u32_e32 v1, vcc, 0, v71, vcc
	ds_bpermute_b32 v18, v111, v17
	global_store_short v[0:1], v2, off offset:1024 sc1
	v_mul_f32_e32 v2, v35, v16
	v_mul_f32_e32 v2, v108, v2
	v_cvt_pk_bf16_f32 v2, v2, s0
	global_store_short v[0:1], v2, off offset:1088 sc1
	v_mul_f32_e32 v2, v19, v16
	v_mul_f32_e32 v2, v107, v2
	s_waitcnt lgkmcnt(0)
	v_add_f32_e32 v17, v17, v18
	v_cvt_pk_bf16_f32 v2, v2, s0
	ds_bpermute_b32 v18, v110, v17
	global_store_short v[0:1], v2, off offset:1152 sc1
	v_mul_f32_e32 v2, v3, v16
	v_mul_f32_e32 v16, v37, v37
	v_fmac_f32_e32 v16, v53, v53
	v_fmac_f32_e32 v16, v21, v21
	v_fmac_f32_e32 v16, v5, v5
	s_waitcnt lgkmcnt(0)
	v_add_f32_e32 v3, v17, v18
	ds_bpermute_b32 v17, v112, v16
	v_fmamk_f32 v3, v3, 0x3c000000, v104
	v_rsq_f32_e32 v3, v3
	v_mul_f32_e32 v2, v106, v2
	v_cvt_pk_bf16_f32 v2, v2, s0
	s_waitcnt lgkmcnt(0)
	v_add_f32_e32 v16, v16, v17
	ds_bpermute_b32 v17, v113, v16
	global_store_short v[0:1], v2, off offset:1216 sc1
	v_mul_f32_e32 v0, v52, v3
	v_mul_f32_e32 v0, v109, v0
	v_cvt_pk_bf16_f32 v2, v0, s0
	s_waitcnt lgkmcnt(0)
	v_add_f32_e32 v16, v16, v17
	ds_bpermute_b32 v17, v114, v16
	v_add_co_u32_e32 v0, vcc, s56, v70
	s_waitcnt lgkmcnt(0)
	v_add_f32_e32 v16, v16, v17
	v_addc_co_u32_e32 v1, vcc, 0, v71, vcc
	global_store_short v[0:1], v2, off sc1
	v_mul_f32_e32 v2, v36, v3
	v_mul_f32_e32 v2, v108, v2
	ds_bpermute_b32 v17, v111, v16
	v_cvt_pk_bf16_f32 v2, v2, s0
	global_store_short v[0:1], v2, off offset:64 sc1
	v_mul_f32_e32 v2, v20, v3
	v_mul_f32_e32 v2, v107, v2
	v_cvt_pk_bf16_f32 v2, v2, s0
	global_store_short v[0:1], v2, off offset:128 sc1
	v_mul_f32_e32 v2, v4, v3
	s_waitcnt lgkmcnt(0)
	v_add_f32_e32 v3, v16, v17
	v_mul_f32_e32 v16, v38, v38
	v_fmac_f32_e32 v16, v54, v54
	v_fmac_f32_e32 v16, v22, v22
	v_fmac_f32_e32 v16, v6, v6
	ds_bpermute_b32 v4, v110, v3
	ds_bpermute_b32 v17, v112, v16
	v_mul_f32_e32 v2, v106, v2
	v_cvt_pk_bf16_f32 v2, v2, s0
	global_store_short v[0:1], v2, off offset:192 sc1
	s_waitcnt lgkmcnt(1)
	v_add_f32_e32 v3, v3, v4
	s_waitcnt lgkmcnt(0)
	v_add_f32_e32 v4, v16, v17
	ds_bpermute_b32 v16, v113, v4
	v_fmamk_f32 v3, v3, 0x3c000000, v104
	v_rsq_f32_e32 v3, v3
	s_waitcnt lgkmcnt(0)
	v_add_f32_e32 v4, v4, v16
	ds_bpermute_b32 v16, v114, v4
	v_mul_f32_e32 v2, v53, v3
	v_mul_f32_e32 v2, v109, v2
	v_cvt_pk_bf16_f32 v2, v2, s0
	global_store_short v[0:1], v2, off offset:3072 sc1
	s_waitcnt lgkmcnt(0)
	v_add_f32_e32 v4, v4, v16
	ds_bpermute_b32 v16, v111, v4
	v_mul_f32_e32 v2, v37, v3
	v_mul_f32_e32 v2, v108, v2
	v_cvt_pk_bf16_f32 v2, v2, s0
	global_store_short v[0:1], v2, off offset:3136 sc1
	s_waitcnt lgkmcnt(0)
	v_add_f32_e32 v4, v4, v16
	ds_bpermute_b32 v16, v110, v4
	v_mul_f32_e32 v2, v21, v3
	v_mul_f32_e32 v2, v107, v2
	v_cvt_pk_bf16_f32 v2, v2, s0
	global_store_short v[0:1], v2, off offset:3200 sc1
	v_mul_f32_e32 v2, v5, v3
	s_waitcnt lgkmcnt(0)
	v_add_f32_e32 v3, v4, v16
	v_mul_f32_e32 v4, v39, v39
	v_fmac_f32_e32 v4, v55, v55
	v_fmac_f32_e32 v4, v23, v23
	v_fmac_f32_e32 v4, v7, v7
	ds_bpermute_b32 v5, v112, v4
	v_fmamk_f32 v3, v3, 0x3c000000, v104
	v_rsq_f32_e32 v3, v3
	v_mul_f32_e32 v2, v106, v2
	v_cvt_pk_bf16_f32 v2, v2, s0
	s_waitcnt lgkmcnt(0)
	v_add_f32_e32 v4, v4, v5
	ds_bpermute_b32 v5, v113, v4
	global_store_short v[0:1], v2, off offset:3264 sc1
	v_mul_f32_e32 v0, v54, v3
	v_mul_f32_e32 v0, v109, v0
	v_cvt_pk_bf16_f32 v2, v0, s0
	s_waitcnt lgkmcnt(0)
	v_add_f32_e32 v4, v4, v5
	ds_bpermute_b32 v5, v114, v4
	v_add_co_u32_e32 v0, vcc, s57, v70
	s_waitcnt lgkmcnt(0)
	v_add_f32_e32 v4, v4, v5
	ds_bpermute_b32 v5, v111, v4
	v_addc_co_u32_e32 v1, vcc, 0, v71, vcc
	global_store_short v[0:1], v2, off offset:2048 sc1
	v_mul_f32_e32 v2, v38, v3
	s_waitcnt lgkmcnt(0)
	v_add_f32_e32 v4, v4, v5
	v_mul_f32_e32 v2, v108, v2
	ds_bpermute_b32 v5, v110, v4
	v_cvt_pk_bf16_f32 v2, v2, s0
	global_store_short v[0:1], v2, off offset:2112 sc1
	v_mul_f32_e32 v2, v22, v3
	v_mul_f32_e32 v2, v107, v2
	v_cvt_pk_bf16_f32 v2, v2, s0
	global_store_short v[0:1], v2, off offset:2176 sc1
	v_mul_f32_e32 v2, v6, v3
	s_waitcnt lgkmcnt(0)
	v_add_f32_e32 v3, v4, v5
	v_mul_f32_e32 v4, v40, v40
	v_fmac_f32_e32 v4, v56, v56
	v_fmac_f32_e32 v4, v24, v24
	v_fmac_f32_e32 v4, v8, v8
	ds_bpermute_b32 v5, v112, v4
	v_fmamk_f32 v3, v3, 0x3c000000, v104
	v_rsq_f32_e32 v3, v3
	v_mul_f32_e32 v2, v106, v2
	v_cvt_pk_bf16_f32 v2, v2, s0
	s_waitcnt lgkmcnt(0)
	v_add_f32_e32 v4, v4, v5
	ds_bpermute_b32 v5, v113, v4
	global_store_short v[0:1], v2, off offset:2240 sc1
	v_mul_f32_e32 v0, v55, v3
	v_mul_f32_e32 v0, v109, v0
	v_cvt_pk_bf16_f32 v2, v0, s0
	s_waitcnt lgkmcnt(0)
	v_add_f32_e32 v4, v4, v5
	ds_bpermute_b32 v5, v114, v4
	v_add_co_u32_e32 v0, vcc, s58, v70
	s_waitcnt lgkmcnt(0)
	v_add_f32_e32 v4, v4, v5
	ds_bpermute_b32 v5, v111, v4
	v_addc_co_u32_e32 v1, vcc, 0, v71, vcc
	global_store_short v[0:1], v2, off offset:1024 sc1
	v_mul_f32_e32 v2, v39, v3
	s_waitcnt lgkmcnt(0)
	v_add_f32_e32 v4, v4, v5
	v_mul_f32_e32 v2, v108, v2
	ds_bpermute_b32 v5, v110, v4
	v_cvt_pk_bf16_f32 v2, v2, s0
	global_store_short v[0:1], v2, off offset:1088 sc1
	v_mul_f32_e32 v2, v23, v3
	v_mul_f32_e32 v2, v107, v2
	v_cvt_pk_bf16_f32 v2, v2, s0
	global_store_short v[0:1], v2, off offset:1152 sc1
	v_mul_f32_e32 v2, v7, v3
	s_waitcnt lgkmcnt(0)
	v_add_f32_e32 v3, v4, v5
	v_mul_f32_e32 v4, v41, v41
	v_fmac_f32_e32 v4, v57, v57
	v_fmac_f32_e32 v4, v25, v25
	v_fmac_f32_e32 v4, v9, v9
	ds_bpermute_b32 v5, v112, v4
	v_fmamk_f32 v3, v3, 0x3c000000, v104
	v_rsq_f32_e32 v3, v3
	v_mul_f32_e32 v2, v106, v2
	v_cvt_pk_bf16_f32 v2, v2, s0
	s_waitcnt lgkmcnt(0)
	v_add_f32_e32 v4, v4, v5
	ds_bpermute_b32 v5, v113, v4
	global_store_short v[0:1], v2, off offset:1216 sc1
	v_mul_f32_e32 v0, v56, v3
	v_mul_f32_e32 v0, v109, v0
	v_cvt_pk_bf16_f32 v2, v0, s0
	s_waitcnt lgkmcnt(0)
	v_add_f32_e32 v4, v4, v5
	ds_bpermute_b32 v5, v114, v4
	v_add_co_u32_e32 v0, vcc, s59, v70
	s_waitcnt lgkmcnt(0)
	v_add_f32_e32 v4, v4, v5
	v_addc_co_u32_e32 v1, vcc, 0, v71, vcc
	global_store_short v[0:1], v2, off sc1
	v_mul_f32_e32 v2, v40, v3
	v_mul_f32_e32 v2, v108, v2
	ds_bpermute_b32 v5, v111, v4
	v_cvt_pk_bf16_f32 v2, v2, s0
	global_store_short v[0:1], v2, off offset:64 sc1
	v_mul_f32_e32 v2, v24, v3
	v_mul_f32_e32 v2, v107, v2
	v_cvt_pk_bf16_f32 v2, v2, s0
	global_store_short v[0:1], v2, off offset:128 sc1
	v_mul_f32_e32 v2, v8, v3
	s_waitcnt lgkmcnt(0)
	v_add_f32_e32 v3, v4, v5
	v_mul_f32_e32 v5, v42, v42
	v_fmac_f32_e32 v5, v58, v58
	v_fmac_f32_e32 v5, v26, v26
	v_fmac_f32_e32 v5, v10, v10
	ds_bpermute_b32 v4, v110, v3
	ds_bpermute_b32 v6, v112, v5
	v_mul_f32_e32 v2, v106, v2
	v_cvt_pk_bf16_f32 v2, v2, s0
	global_store_short v[0:1], v2, off offset:192 sc1
	s_waitcnt lgkmcnt(1)
	v_add_f32_e32 v3, v3, v4
	s_waitcnt lgkmcnt(0)
	v_add_f32_e32 v4, v5, v6
	ds_bpermute_b32 v5, v113, v4
	v_fmamk_f32 v3, v3, 0x3c000000, v104
	v_rsq_f32_e32 v3, v3
	s_waitcnt lgkmcnt(0)
	v_add_f32_e32 v4, v4, v5
	ds_bpermute_b32 v5, v114, v4
	v_mul_f32_e32 v2, v57, v3
	v_mul_f32_e32 v2, v109, v2
	v_cvt_pk_bf16_f32 v2, v2, s0
	global_store_short v[0:1], v2, off offset:3072 sc1
	s_waitcnt lgkmcnt(0)
	v_add_f32_e32 v4, v4, v5
	ds_bpermute_b32 v5, v111, v4
	v_mul_f32_e32 v2, v41, v3
	v_mul_f32_e32 v2, v108, v2
	v_cvt_pk_bf16_f32 v2, v2, s0
	global_store_short v[0:1], v2, off offset:3136 sc1
	s_waitcnt lgkmcnt(0)
	v_add_f32_e32 v4, v4, v5
	ds_bpermute_b32 v5, v110, v4
	v_mul_f32_e32 v2, v25, v3
	v_mul_f32_e32 v2, v107, v2
	v_cvt_pk_bf16_f32 v2, v2, s0
	global_store_short v[0:1], v2, off offset:3200 sc1
	v_mul_f32_e32 v2, v9, v3
	s_waitcnt lgkmcnt(0)
	v_add_f32_e32 v3, v4, v5
	v_mul_f32_e32 v4, v43, v43
	v_fmac_f32_e32 v4, v59, v59
	v_fmac_f32_e32 v4, v27, v27
	v_fmac_f32_e32 v4, v11, v11
	ds_bpermute_b32 v5, v112, v4
	v_fmamk_f32 v3, v3, 0x3c000000, v104
	v_rsq_f32_e32 v3, v3
	v_mul_f32_e32 v2, v106, v2
	v_cvt_pk_bf16_f32 v2, v2, s0
	s_waitcnt lgkmcnt(0)
	v_add_f32_e32 v4, v4, v5
	ds_bpermute_b32 v5, v113, v4
	global_store_short v[0:1], v2, off offset:3264 sc1
	v_mul_f32_e32 v0, v58, v3
	v_mul_f32_e32 v0, v109, v0
	v_cvt_pk_bf16_f32 v2, v0, s0
	s_waitcnt lgkmcnt(0)
	v_add_f32_e32 v4, v4, v5
	ds_bpermute_b32 v5, v114, v4
	v_add_co_u32_e32 v0, vcc, s60, v70
	s_waitcnt lgkmcnt(0)
	v_add_f32_e32 v4, v4, v5
	ds_bpermute_b32 v5, v111, v4
	v_addc_co_u32_e32 v1, vcc, 0, v71, vcc
	global_store_short v[0:1], v2, off offset:2048 sc1
	v_mul_f32_e32 v2, v42, v3
	s_waitcnt lgkmcnt(0)
	v_add_f32_e32 v4, v4, v5
	v_mul_f32_e32 v2, v108, v2
	ds_bpermute_b32 v5, v110, v4
	v_cvt_pk_bf16_f32 v2, v2, s0
	global_store_short v[0:1], v2, off offset:2112 sc1
	v_mul_f32_e32 v2, v26, v3
	v_mul_f32_e32 v2, v107, v2
	v_cvt_pk_bf16_f32 v2, v2, s0
	global_store_short v[0:1], v2, off offset:2176 sc1
	v_mul_f32_e32 v2, v10, v3
	s_waitcnt lgkmcnt(0)
	v_add_f32_e32 v3, v4, v5
	v_mul_f32_e32 v4, v44, v44
	v_fmac_f32_e32 v4, v60, v60
	v_fmac_f32_e32 v4, v28, v28
	v_fmac_f32_e32 v4, v12, v12
	ds_bpermute_b32 v5, v112, v4
	v_fmamk_f32 v3, v3, 0x3c000000, v104
	v_rsq_f32_e32 v3, v3
	v_mul_f32_e32 v2, v106, v2
	v_cvt_pk_bf16_f32 v2, v2, s0
	s_waitcnt lgkmcnt(0)
	v_add_f32_e32 v4, v4, v5
	ds_bpermute_b32 v5, v113, v4
	global_store_short v[0:1], v2, off offset:2240 sc1
	v_mul_f32_e32 v0, v59, v3
	v_mul_f32_e32 v0, v109, v0
	v_cvt_pk_bf16_f32 v2, v0, s0
	s_waitcnt lgkmcnt(0)
	v_add_f32_e32 v4, v4, v5
	ds_bpermute_b32 v5, v114, v4
	v_add_co_u32_e32 v0, vcc, s61, v70
	s_waitcnt lgkmcnt(0)
	v_add_f32_e32 v4, v4, v5
	v_addc_co_u32_e32 v1, vcc, 0, v71, vcc
	global_store_short v[0:1], v2, off offset:1024 sc1
	v_mul_f32_e32 v2, v43, v3
	v_mul_f32_e32 v2, v108, v2
	ds_bpermute_b32 v5, v111, v4
	v_cvt_pk_bf16_f32 v2, v2, s0
	global_store_short v[0:1], v2, off offset:1088 sc1
	v_mul_f32_e32 v2, v27, v3
	v_mul_f32_e32 v2, v107, v2
	v_cvt_pk_bf16_f32 v2, v2, s0
	global_store_short v[0:1], v2, off offset:1152 sc1
	v_mul_f32_e32 v2, v11, v3
	s_waitcnt lgkmcnt(0)
	v_add_f32_e32 v3, v4, v5
	v_mul_f32_e32 v5, v45, v45
	v_fmac_f32_e32 v5, v61, v61
	v_fmac_f32_e32 v5, v29, v29
	v_fmac_f32_e32 v5, v13, v13
	ds_bpermute_b32 v4, v110, v3
	ds_bpermute_b32 v6, v112, v5
	v_mul_f32_e32 v2, v106, v2
	v_cvt_pk_bf16_f32 v2, v2, s0
	global_store_short v[0:1], v2, off offset:1216 sc1
	s_waitcnt lgkmcnt(1)
	v_add_f32_e32 v3, v3, v4
	s_waitcnt lgkmcnt(0)
	v_add_f32_e32 v4, v5, v6
	ds_bpermute_b32 v5, v113, v4
	v_fmamk_f32 v3, v3, 0x3c000000, v104
	v_rsq_f32_e32 v3, v3
	s_waitcnt lgkmcnt(0)
	v_add_f32_e32 v4, v4, v5
	ds_bpermute_b32 v5, v114, v4
	v_mul_f32_e32 v0, v60, v3
	v_mul_f32_e32 v0, v109, v0
	v_cvt_pk_bf16_f32 v2, v0, s0
	v_add_co_u32_e32 v0, vcc, s65, v70
	s_waitcnt lgkmcnt(0)
	v_add_f32_e32 v4, v4, v5
	ds_bpermute_b32 v5, v111, v4
	v_addc_co_u32_e32 v1, vcc, 0, v71, vcc
	global_store_short v[0:1], v2, off sc1
	v_mul_f32_e32 v2, v44, v3
	s_waitcnt lgkmcnt(0)
	v_add_f32_e32 v4, v4, v5
	v_mul_f32_e32 v2, v108, v2
	ds_bpermute_b32 v5, v110, v4
	v_cvt_pk_bf16_f32 v2, v2, s0
	global_store_short v[0:1], v2, off offset:64 sc1
	v_mul_f32_e32 v2, v28, v3
	v_mul_f32_e32 v2, v107, v2
	v_cvt_pk_bf16_f32 v2, v2, s0
	global_store_short v[0:1], v2, off offset:128 sc1
	v_mul_f32_e32 v2, v12, v3
	s_waitcnt lgkmcnt(0)
	v_add_f32_e32 v3, v4, v5
	v_mul_f32_e32 v4, v46, v46
	v_fmac_f32_e32 v4, v62, v62
	v_fmac_f32_e32 v4, v30, v30
	v_fmac_f32_e32 v4, v14, v14
	ds_bpermute_b32 v5, v112, v4
	v_fmamk_f32 v3, v3, 0x3c000000, v104
	v_rsq_f32_e32 v3, v3
	v_mul_f32_e32 v2, v106, v2
	v_cvt_pk_bf16_f32 v2, v2, s0
	s_waitcnt lgkmcnt(0)
	v_add_f32_e32 v4, v4, v5
	ds_bpermute_b32 v5, v113, v4
	global_store_short v[0:1], v2, off offset:192 sc1
	v_mul_f32_e32 v2, v61, v3
	v_mul_f32_e32 v2, v109, v2
	v_cvt_pk_bf16_f32 v2, v2, s0
	s_waitcnt lgkmcnt(0)
	v_add_f32_e32 v4, v4, v5
	ds_bpermute_b32 v5, v114, v4
	global_store_short v[0:1], v2, off offset:3072 sc1
	v_mul_f32_e32 v2, v45, v3
	v_mul_f32_e32 v2, v108, v2
	v_cvt_pk_bf16_f32 v2, v2, s0
	s_waitcnt lgkmcnt(0)
	v_add_f32_e32 v4, v4, v5
	ds_bpermute_b32 v5, v111, v4
	global_store_short v[0:1], v2, off offset:3136 sc1
	v_mul_f32_e32 v2, v29, v3
	v_mul_f32_e32 v2, v107, v2
	v_cvt_pk_bf16_f32 v2, v2, s0
	global_store_short v[0:1], v2, off offset:3200 sc1
	v_mul_f32_e32 v2, v13, v3
	s_waitcnt lgkmcnt(0)
	v_add_f32_e32 v3, v4, v5
	v_mul_f32_e32 v5, v47, v47
	v_fmac_f32_e32 v5, v63, v63
	v_fmac_f32_e32 v5, v31, v31
	v_fmac_f32_e32 v5, v15, v15
	ds_bpermute_b32 v4, v110, v3
	ds_bpermute_b32 v6, v112, v5
	v_mul_f32_e32 v2, v106, v2
	v_cvt_pk_bf16_f32 v2, v2, s0
	global_store_short v[0:1], v2, off offset:3264 sc1
	s_waitcnt lgkmcnt(1)
	v_add_f32_e32 v3, v3, v4
	s_waitcnt lgkmcnt(0)
	v_add_f32_e32 v4, v5, v6
	ds_bpermute_b32 v5, v113, v4
	v_fmamk_f32 v3, v3, 0x3c000000, v104
	v_rsq_f32_e32 v3, v3
	s_waitcnt lgkmcnt(0)
	v_add_f32_e32 v4, v4, v5
	ds_bpermute_b32 v5, v114, v4
	v_mul_f32_e32 v0, v62, v3
	v_mul_f32_e32 v0, v109, v0
	v_cvt_pk_bf16_f32 v2, v0, s0
	v_add_co_u32_e32 v0, vcc, s66, v70
	s_waitcnt lgkmcnt(0)
	v_add_f32_e32 v4, v4, v5
	ds_bpermute_b32 v5, v111, v4
	v_addc_co_u32_e32 v1, vcc, 0, v71, vcc
	global_store_short v[0:1], v2, off offset:2048 sc1
	v_mul_f32_e32 v2, v46, v3
	s_waitcnt lgkmcnt(0)
	v_add_f32_e32 v4, v4, v5
	v_mul_f32_e32 v2, v108, v2
	ds_bpermute_b32 v5, v110, v4
	v_cvt_pk_bf16_f32 v2, v2, s0
	global_store_short v[0:1], v2, off offset:2112 sc1
	v_mul_f32_e32 v2, v30, v3
	v_mul_f32_e32 v2, v107, v2
	v_cvt_pk_bf16_f32 v2, v2, s0
	global_store_short v[0:1], v2, off offset:2176 sc1
	v_mul_f32_e32 v2, v14, v3
	s_waitcnt lgkmcnt(0)
	v_add_f32_e32 v3, v4, v5
	v_fmamk_f32 v3, v3, 0x3c000000, v104
	v_rsq_f32_e32 v3, v3
	v_mul_f32_e32 v2, v106, v2
	v_cvt_pk_bf16_f32 v2, v2, s0
	global_store_short v[0:1], v2, off offset:2240 sc1
	v_mul_f32_e32 v0, v63, v3
	v_mul_f32_e32 v0, v109, v0
	v_cvt_pk_bf16_f32 v2, v0, s0
	v_add_co_u32_e32 v0, vcc, s67, v70
	s_nop 1
	v_addc_co_u32_e32 v1, vcc, 0, v71, vcc
	global_store_short v[0:1], v2, off offset:1024 sc1
	v_mul_f32_e32 v2, v47, v3
	v_mul_f32_e32 v2, v108, v2
	v_cvt_pk_bf16_f32 v2, v2, s0
	global_store_short v[0:1], v2, off offset:1088 sc1
	v_mul_f32_e32 v2, v31, v3
	v_mul_f32_e32 v2, v107, v2
	v_cvt_pk_bf16_f32 v2, v2, s0
	global_store_short v[0:1], v2, off offset:1152 sc1
	v_mul_f32_e32 v2, v15, v3
	v_mul_f32_e32 v2, v106, v2
	v_cvt_pk_bf16_f32 v2, v2, s0
	global_store_short v[0:1], v2, off offset:1216 sc1
	s_branch .LBB0_646
.LBB0_655:
	s_cmp_gt_i32 s17, 5
	s_cselect_b64 s[6:7], -1, 0
	s_and_b64 s[0:1], s[4:5], s[6:7]
	s_andn2_b64 vcc, exec, s[0:1]
	s_cbranch_vccnz .LBB0_667
	s_waitcnt vmcnt(0)
	v_or_b32_e32 v0, v201, v200
	s_movk_i32 s0, 0x3ff
	v_and_or_b32 v0, v0, s0, v199
	v_cmp_eq_u32_e32 vcc, 0, v0
	s_waitcnt lgkmcnt(0)
	s_barrier
	s_and_saveexec_b64 s[0:1], vcc
	s_cbranch_execz .LBB0_666
	s_add_u32 s4, s14, 0x5be8c00
	s_addc_u32 s5, s15, 0
	s_lshl_b32 s3, s2, 1
	v_mov_b32_e32 v0, s3
	v_mov_b32_e32 v1, 0x9305
	global_store_short v0, v1, s[4:5] sc1
	s_cmp_lg_u32 s2, 0
	s_cbranch_scc1 .Lgbar_wait_4
	s_lshr_b32 s3, s33, 3
	s_bfm_b64 s[8:9], s3, 0
	s_cmpk_gt_u32 s33, 0x1ff
	s_cselect_b64 s[8:9], -1, s[8:9]
	s_mov_b64 exec, -1
	v_mbcnt_lo_u32_b32 v229, -1, 0
	v_mbcnt_hi_u32_b32 v229, -1, v229
	v_lshlrev_b32_e32 v229, 4, v229
	s_mov_b32 s10, 0x93059305
	s_mov_b64 exec, s[8:9]

.LBB0_670:
	ds_bpermute_b32 v0, v209, v193
	v_lshlrev_b64 v[2:3], 11, v[194:195]
	s_mov_b32 s19, s7
	v_lshl_add_u64 v[2:3], s[4:5], 0, v[2:3]
	v_lshl_add_u64 v[2:3], s[18:19], 1, v[2:3]
	s_waitcnt lgkmcnt(0)
	v_add_f32_e32 v0, v193, v0
	v_div_scale_f32 v4, s[20:21], v0, v0, 1.0
	v_rcp_f32_e32 v5, v4
	v_div_scale_f32 v6, vcc, 1.0, v0, 1.0
	v_mov_b32_e32 v193, v1
	v_fma_f32 v7, -v4, v5, 1.0
	v_fmac_f32_e32 v5, v7, v5
	v_mul_f32_e32 v7, v6, v5
	v_fma_f32 v8, -v4, v7, v6
	v_fmac_f32_e32 v7, v8, v5
	v_fma_f32 v4, -v4, v7, v6
	v_div_fmas_f32 v4, v4, v5, v7
	v_div_fixup_f32 v0, v4, v0, 1.0
	v_pk_mul_f32 v[4:5], v[64:65], v[0:1] op_sel_hi:[1,0]
	v_pk_mul_f32 v[6:7], v[66:67], v[0:1] op_sel_hi:[1,0]
	v_pk_mul_f32 v[8:9], v[68:69], v[0:1] op_sel_hi:[1,0]
	v_pk_mul_f32 v[10:11], v[70:71], v[0:1] op_sel_hi:[1,0]
	v_lshl_add_u64 v[2:3], v[2:3], 0, v[192:193]
	v_cvt_pk_bf16_f32 v4, v4, v5
	v_cvt_pk_bf16_f32 v5, v6, v7
	v_pk_mul_f32 v[12:13], v[72:73], v[0:1] op_sel_hi:[1,0]
	v_pk_mul_f32 v[14:15], v[74:75], v[0:1] op_sel_hi:[1,0]
	global_store_dwordx2 v[2:3], v[4:5], off sc1
	v_cvt_pk_bf16_f32 v4, v8, v9
	v_cvt_pk_bf16_f32 v5, v10, v11
	v_pk_mul_f32 v[64:65], v[76:77], v[0:1] op_sel_hi:[1,0]
	v_pk_mul_f32 v[66:67], v[78:79], v[0:1] op_sel_hi:[1,0]
	global_store_dwordx2 v[2:3], v[4:5], off offset:16 sc1
	v_cvt_pk_bf16_f32 v4, v12, v13
	v_cvt_pk_bf16_f32 v5, v14, v15
	v_pk_mul_f32 v[48:49], v[48:49], v[0:1] op_sel_hi:[1,0]
	v_pk_mul_f32 v[50:51], v[50:51], v[0:1] op_sel_hi:[1,0]
	global_store_dwordx2 v[2:3], v[4:5], off offset:32 sc1
	v_cvt_pk_bf16_f32 v4, v64, v65
	v_cvt_pk_bf16_f32 v5, v66, v67
	v_pk_mul_f32 v[52:53], v[52:53], v[0:1] op_sel_hi:[1,0]
	v_pk_mul_f32 v[54:55], v[54:55], v[0:1] op_sel_hi:[1,0]
	global_store_dwordx2 v[2:3], v[4:5], off offset:48 sc1
	v_cvt_pk_bf16_f32 v4, v48, v49
	v_cvt_pk_bf16_f32 v5, v50, v51
	v_pk_mul_f32 v[56:57], v[56:57], v[0:1] op_sel_hi:[1,0]
	v_pk_mul_f32 v[58:59], v[58:59], v[0:1] op_sel_hi:[1,0]
	global_store_dwordx2 v[2:3], v[4:5], off offset:64 sc1
	v_cvt_pk_bf16_f32 v4, v52, v53
	v_cvt_pk_bf16_f32 v5, v54, v55
	v_pk_mul_f32 v[60:61], v[60:61], v[0:1] op_sel_hi:[1,0]
	v_pk_mul_f32 v[62:63], v[62:63], v[0:1] op_sel_hi:[1,0]
	global_store_dwordx2 v[2:3], v[4:5], off offset:80 sc1
	v_cvt_pk_bf16_f32 v4, v56, v57
	v_cvt_pk_bf16_f32 v5, v58, v59
	v_pk_mul_f32 v[32:33], v[32:33], v[0:1] op_sel_hi:[1,0]
	v_pk_mul_f32 v[34:35], v[34:35], v[0:1] op_sel_hi:[1,0]
	global_store_dwordx2 v[2:3], v[4:5], off offset:96 sc1
	v_cvt_pk_bf16_f32 v4, v60, v61
	v_cvt_pk_bf16_f32 v5, v62, v63
	v_pk_mul_f32 v[36:37], v[36:37], v[0:1] op_sel_hi:[1,0]
	v_pk_mul_f32 v[38:39], v[38:39], v[0:1] op_sel_hi:[1,0]
	global_store_dwordx2 v[2:3], v[4:5], off offset:112 sc1
	v_cvt_pk_bf16_f32 v4, v32, v33
	v_cvt_pk_bf16_f32 v5, v34, v35
	v_pk_mul_f32 v[40:41], v[40:41], v[0:1] op_sel_hi:[1,0]
	v_pk_mul_f32 v[42:43], v[42:43], v[0:1] op_sel_hi:[1,0]
	global_store_dwordx2 v[2:3], v[4:5], off offset:128 sc1
	v_cvt_pk_bf16_f32 v4, v36, v37
	v_cvt_pk_bf16_f32 v5, v38, v39
	v_pk_mul_f32 v[44:45], v[44:45], v[0:1] op_sel_hi:[1,0]
	v_pk_mul_f32 v[46:47], v[46:47], v[0:1] op_sel_hi:[1,0]
	global_store_dwordx2 v[2:3], v[4:5], off offset:144 sc1
	v_cvt_pk_bf16_f32 v4, v40, v41
	v_cvt_pk_bf16_f32 v5, v42, v43
	v_pk_mul_f32 v[16:17], v[16:17], v[0:1] op_sel_hi:[1,0]
	v_pk_mul_f32 v[18:19], v[18:19], v[0:1] op_sel_hi:[1,0]
	global_store_dwordx2 v[2:3], v[4:5], off offset:160 sc1
	v_cvt_pk_bf16_f32 v4, v44, v45
	v_cvt_pk_bf16_f32 v5, v46, v47
	v_pk_mul_f32 v[20:21], v[20:21], v[0:1] op_sel_hi:[1,0]
	v_pk_mul_f32 v[22:23], v[22:23], v[0:1] op_sel_hi:[1,0]
	global_store_dwordx2 v[2:3], v[4:5], off offset:176 sc1
	v_cvt_pk_bf16_f32 v4, v16, v17
	v_cvt_pk_bf16_f32 v5, v18, v19
	v_pk_mul_f32 v[24:25], v[24:25], v[0:1] op_sel_hi:[1,0]
	v_pk_mul_f32 v[26:27], v[26:27], v[0:1] op_sel_hi:[1,0]
	global_store_dwordx2 v[2:3], v[4:5], off offset:192 sc1
	v_cvt_pk_bf16_f32 v4, v20, v21
	v_cvt_pk_bf16_f32 v5, v22, v23
	v_pk_mul_f32 v[28:29], v[28:29], v[0:1] op_sel_hi:[1,0]
	v_pk_mul_f32 v[30:31], v[30:31], v[0:1] op_sel_hi:[1,0]
	global_store_dwordx2 v[2:3], v[4:5], off offset:208 sc1
	v_cvt_pk_bf16_f32 v4, v24, v25
	v_cvt_pk_bf16_f32 v5, v26, v27
	s_add_i32 s37, s37, s33
	global_store_dwordx2 v[2:3], v[4:5], off offset:224 sc1
	v_cvt_pk_bf16_f32 v4, v28, v29
	v_cvt_pk_bf16_f32 v5, v30, v31
	s_cmpk_gt_i32 s37, 0x3ff
	global_store_dwordx2 v[2:3], v[4:5], off offset:240 sc1
	s_cbranch_scc1 .LBB0_687

.LBB0_687:
	s_cmp_gt_i32 s17, 6
	s_cselect_b64 s[6:7], -1, 0
	s_and_b64 s[0:1], s[0:1], s[6:7]
	s_andn2_b64 vcc, exec, s[0:1]
	s_cbranch_vccnz .LBB0_699
	s_waitcnt vmcnt(0)
	v_or_b32_e32 v0, v201, v200
	s_movk_i32 s0, 0x3ff
	v_and_or_b32 v0, v0, s0, v199
	v_cmp_eq_u32_e32 vcc, 0, v0
	s_waitcnt lgkmcnt(0)
	s_barrier
	s_and_saveexec_b64 s[0:1], vcc
	s_cbranch_execz .LBB0_698
	s_add_u32 s4, s14, 0x5be8c00
	s_addc_u32 s5, s15, 0
	s_lshl_b32 s3, s2, 1
	v_mov_b32_e32 v0, s3
	v_mov_b32_e32 v1, 0x9306
	global_store_short v0, v1, s[4:5] sc1
	s_cmp_lg_u32 s2, 0
	s_cbranch_scc1 .Lgbar_wait_5
	s_lshr_b32 s3, s33, 3
	s_bfm_b64 s[8:9], s3, 0
	s_cmpk_gt_u32 s33, 0x1ff
	s_cselect_b64 s[8:9], -1, s[8:9]
	s_mov_b64 exec, -1
	v_mbcnt_lo_u32_b32 v229, -1, 0
	v_mbcnt_hi_u32_b32 v229, -1, v229
	v_lshlrev_b32_e32 v229, 4, v229
	s_mov_b32 s10, 0x93069306
	s_mov_b64 exec, s[8:9]

.LBB0_699:
	s_cmp_lt_i32 s16, 7
	s_cselect_b64 s[4:5], -1, 0
	s_and_b64 s[0:1], s[4:5], s[6:7]
	s_andn2_b64 vcc, exec, s[0:1]
	s_cbranch_vccnz .LBB0_739
	s_ashr_i32 s0, s2, 31
	s_and_b32 s0, s0, s33
	s_add_i32 s3, s0, s2
	s_cmpk_gt_i32 s3, 0x3ff
	s_cbranch_scc1 .LBB0_739
	v_lshrrev_b32_e32 v0, 3, v199
	v_lshrrev_b32_e32 v1, 5, v199
	v_bfe_u32 v4, v199, 1, 3
	v_lshlrev_b32_e32 v5, 4, v199
	v_bfe_u32 v2, v199, 5, 1
	v_xor_b32_e32 v6, v5, v199
	v_lshlrev_b32_e32 v7, 11, v0
	s_movk_i32 s0, 0x70
	v_bitop3_b32 v1, v1, v4, 1 bitop3:0x6c
	v_and_or_b32 v64, v6, s0, v7
	v_lshlrev_b32_e32 v7, 4, v1
	v_bitop3_b32 v1, v2, v4, 2 bitop3:0x36
	v_lshrrev_b32_e32 v3, 1, v199
	v_lshlrev_b32_e32 v9, 4, v1
	v_bitop3_b32 v1, v2, v4, 4 bitop3:0x36
	v_mov_b32_e32 v65, 0
	v_and_b32_e32 v3, 0x1e0, v3
	v_lshlrev_b32_e32 v10, 4, v1
	v_bitop3_b32 v1, v2, v4, 6 bitop3:0x36
	v_and_b32_e32 v140, 31, v199
	v_lshlrev_b32_e32 v2, 4, v1
	v_and_or_b32 v141, v0, 4, v3
	v_lshl_add_u64 v[0:1], s[14:15], 0, v[64:65]
	s_mov_b64 s[8:9], 0xb79f000
	s_add_u32 s10, s14, 0x5c4e000
	v_or_b32_e32 v6, v3, v140
	v_lshl_add_u64 v[66:67], v[0:1], 0, s[8:9]
	s_mov_b64 s[8:9], 0x3a0000
	s_addc_u32 s11, s15, 0
	v_lshl_add_u32 v6, v6, 7, 0
	v_lshl_add_u32 v8, v140, 7, 0
	v_lshl_add_u64 v[68:69], v[0:1], 0, s[8:9]
	s_add_u32 s8, s14, 0x679f000
	v_add_u32_e32 v142, 0, v5
	v_mbcnt_lo_u32_b32 v0, -1, 0
	s_mov_b32 s7, 0
	v_cmp_eq_u32_e64 s[0:1], 0, v140
	s_addc_u32 s9, s15, 0
	v_add_u32_e32 v143, 0x4000, v142
	s_mov_b64 s[18:19], 0x10000
	s_waitcnt vmcnt(24)
	v_add_u32_e32 v144, 0x1000, v142
	v_add_u32_e32 v145, 0x5000, v142
	s_mov_b64 s[20:21], 0x20000
	v_add_u32_e32 v146, 0x2000, v142
	v_add_u32_e32 v147, 0x6000, v142
	s_mov_b64 s[22:23], 0x30000
	v_add_u32_e32 v148, 0x3000, v142
	v_add_u32_e32 v149, 0x7000, v142
	s_mov_b64 s[24:25], 0xb79f080
	s_mov_b64 s[26:27], 0x3a0080
	v_add_u32_e32 v150, 0x8000, v142
	v_add_u32_e32 v151, 0xc000, v142
	s_mov_b64 s[28:29], 0xb7af080
	s_waitcnt vmcnt(23)
	v_add_u32_e32 v152, 0x9000, v142
	s_mov_b64 s[30:31], 0x3b0080
	v_add_u32_e32 v153, 0xd000, v142
	s_mov_b64 s[34:35], 0xb7bf080
	v_add_u32_e32 v154, 0xa000, v142
	s_mov_b64 s[36:37], 0x3c0080
	v_add_u32_e32 v155, 0xe000, v142
	s_mov_b64 s[38:39], 0xb7cf080
	s_waitcnt vmcnt(22)
	v_add_u32_e32 v156, 0xb000, v142
	s_mov_b64 s[40:41], 0x3d0080
	v_add_u32_e32 v157, 0xf000, v142
	v_add_u32_e32 v158, v6, v7
	v_add_u32_e32 v159, v8, v7
	s_waitcnt vmcnt(21)
	v_add_u32_e32 v160, v6, v9
	v_add_u32_e32 v161, v8, v9
	v_add_u32_e32 v162, v6, v10
	v_add_u32_e32 v163, v8, v10
	s_waitcnt vmcnt(19)
	v_add_u32_e32 v164, v6, v2
	v_add_u32_e32 v165, v8, v2
	s_mov_b64 s[42:43], 0xb79f100
	s_mov_b64 s[44:45], 0x3a0100
	s_mov_b64 s[46:47], 0xb7af100
	s_mov_b64 s[48:49], 0x3b0100
	s_mov_b64 s[50:51], 0xb7bf100
	s_mov_b64 s[52:53], 0x3c0100
	s_mov_b64 s[54:55], 0xb7cf100
	s_mov_b64 s[56:57], 0x3d0100
	s_add_i32 s68, 0, 0x12070
	v_mbcnt_hi_u32_b32 v166, -1, v0
	s_mov_b32 s39, 0
	s_branch .LBB0_703

.LBB0_703:
	s_ashr_i32 s6, s3, 31
	s_lshr_b32 s6, s6, 26
	s_add_i32 s6, s3, s6
	s_ashr_i32 s58, s6, 6
	s_andn2_b32 s6, s6, 63
	s_sub_i32 s6, s3, s6
	s_ashr_i32 s59, s6, 31
	s_lshr_b32 s59, s59, 29
	s_add_i32 s59, s6, s59
	s_ashr_i32 s69, s59, 3
	s_and_b32 s59, s59, -8
	s_lshl_b32 s58, s58, 3
	s_sub_i32 s6, s6, s59
	s_add_i32 s6, s6, s58
	s_lshl_b32 s64, s6, 7
	s_ashr_i32 s65, s64, 31
	s_lshl_b32 s66, s69, 7
	s_lshl_b64 s[58:59], s[64:65], 11
	s_ashr_i32 s67, s66, 31
	s_cmp_eq_u32 s39, 1
	s_cbranch_scc1 .Lgk_pfhead_p6
	s_lshl_b32 s38, s64, 11
	s_add_u32 s18, s14, s38
	s_addc_u32 s19, s15, 0
	s_add_u32 s18, s18, 0xb79f000
	s_addc_u32 s19, s19, 0
	s_add_u32 s20, s18, 0x10000
	s_addc_u32 s21, s19, 0
	s_add_u32 s22, s20, 0x10000
	s_addc_u32 s23, s21, 0
	s_add_u32 s24, s22, 0x10000
	s_addc_u32 s25, s23, 0
	s_lshl_b32 s38, s66, 11
	s_add_u32 s26, s14, s38
	s_addc_u32 s27, s15, 0
	s_add_u32 s26, s26, 0x3a0000
	s_addc_u32 s27, s27, 0
	s_add_u32 s28, s26, 0x10000
	s_addc_u32 s29, s27, 0
	s_add_u32 s30, s28, 0x10000
	s_addc_u32 s31, s29, 0
	s_add_u32 s34, s30, 0x10000
	s_addc_u32 s35, s31, 0
	v_readfirstlane_b32 s36, v142
	v_mov_b32_e32 v254, v64
	s_mov_b32 m0, s36
	s_nop 0
	global_load_lds_dwordx4 v254, s[18:19]
	s_add_u32 m0, m0, 0x1000
	s_nop 0
	global_load_lds_dwordx4 v254, s[20:21]
	s_add_u32 m0, m0, 0x1000
	s_nop 0
	global_load_lds_dwordx4 v254, s[22:23]
	s_add_u32 m0, m0, 0x1000
	s_nop 0
	global_load_lds_dwordx4 v254, s[24:25]
	s_add_u32 m0, m0, 0x1000
	s_nop 0
	global_load_lds_dwordx4 v254, s[26:27]
	s_add_u32 m0, m0, 0x1000
	s_nop 0
	global_load_lds_dwordx4 v254, s[28:29]
	s_add_u32 m0, m0, 0x1000
	s_nop 0
	global_load_lds_dwordx4 v254, s[30:31]
	s_add_u32 m0, m0, 0x1000
	s_nop 0
	global_load_lds_dwordx4 v254, s[34:35]
	v_add_u32_e32 v254, 0x80, v254
	s_add_u32 m0, s36, 0x8000
	s_nop 0
	global_load_lds_dwordx4 v254, s[18:19]
	s_add_u32 m0, m0, 0x1000
	s_nop 0
	global_load_lds_dwordx4 v254, s[20:21]
	s_add_u32 m0, m0, 0x1000
	s_nop 0
	global_load_lds_dwordx4 v254, s[22:23]
	s_add_u32 m0, m0, 0x1000
	s_nop 0
	global_load_lds_dwordx4 v254, s[24:25]
	s_add_u32 m0, m0, 0x1000
	s_nop 0
	global_load_lds_dwordx4 v254, s[26:27]
	s_add_u32 m0, m0, 0x1000
	s_nop 0
	global_load_lds_dwordx4 v254, s[28:29]
	s_add_u32 m0, m0, 0x1000
	s_nop 0
	global_load_lds_dwordx4 v254, s[30:31]
	s_add_u32 m0, m0, 0x1000
	s_nop 0
	global_load_lds_dwordx4 v254, s[34:35]
	v_add_u32_e32 v254, 0x80, v254
.Lgk_pfhead_p6:
	v_mov_b32_e32 v48, 0
	v_mov_b32_e32 v49, 0
	v_mov_b32_e32 v50, 0
	v_mov_b32_e32 v51, 0
	v_mov_b32_e32 v52, 0
	v_mov_b32_e32 v53, 0
	v_mov_b32_e32 v54, 0
	v_mov_b32_e32 v55, 0
	v_mov_b32_e32 v56, 0
	v_mov_b32_e32 v57, 0
	v_mov_b32_e32 v58, 0
	v_mov_b32_e32 v59, 0
	v_mov_b32_e32 v60, 0
	v_mov_b32_e32 v61, 0
	v_mov_b32_e32 v62, 0
	v_mov_b32_e32 v63, 0
	v_mov_b32_e32 v32, 0
	v_mov_b32_e32 v33, 0
	v_mov_b32_e32 v34, 0
	v_mov_b32_e32 v35, 0
	v_mov_b32_e32 v36, 0
	v_mov_b32_e32 v37, 0
	v_mov_b32_e32 v38, 0
	v_mov_b32_e32 v39, 0
	v_mov_b32_e32 v40, 0
	v_mov_b32_e32 v41, 0
	v_mov_b32_e32 v42, 0
	v_mov_b32_e32 v43, 0
	v_mov_b32_e32 v44, 0
	v_mov_b32_e32 v45, 0
	v_mov_b32_e32 v46, 0
	v_mov_b32_e32 v47, 0
	v_mov_b32_e32 v16, 0
	v_mov_b32_e32 v17, 0
	v_mov_b32_e32 v18, 0
	v_mov_b32_e32 v19, 0
	v_mov_b32_e32 v20, 0
	v_mov_b32_e32 v21, 0
	v_mov_b32_e32 v22, 0
	v_mov_b32_e32 v23, 0
	v_mov_b32_e32 v24, 0
	v_mov_b32_e32 v25, 0
	v_mov_b32_e32 v26, 0
	v_mov_b32_e32 v27, 0
	v_mov_b32_e32 v28, 0
	v_mov_b32_e32 v29, 0
	v_mov_b32_e32 v30, 0
	v_mov_b32_e32 v31, 0
	v_mov_b32_e32 v0, 0
	v_mov_b32_e32 v1, 0
	v_mov_b32_e32 v2, 0
	v_mov_b32_e32 v3, 0
	v_mov_b32_e32 v4, 0
	v_mov_b32_e32 v5, 0
	v_mov_b32_e32 v6, 0
	v_mov_b32_e32 v7, 0
	v_mov_b32_e32 v8, 0
	v_mov_b32_e32 v9, 0
	v_mov_b32_e32 v10, 0
	v_mov_b32_e32 v11, 0
	v_mov_b32_e32 v12, 0
	v_mov_b32_e32 v13, 0
	v_mov_b32_e32 v14, 0
	v_mov_b32_e32 v15, 0
	s_mov_b32 s37, 7
.Lgk_loop_p6:
	s_waitcnt vmcnt(8)
	s_barrier
	ds_read_b128 v[70:73], v158
	ds_read_b128 v[74:77], v159 offset:16384
	ds_read_b128 v[78:81], v159 offset:20480
	ds_read_b128 v[82:85], v159 offset:24576
	ds_read_b128 v[86:89], v159 offset:28672
	ds_read_b128 v[90:93], v160
	ds_read_b128 v[94:97], v161 offset:16384
	ds_read_b128 v[98:101], v161 offset:20480
	ds_read_b128 v[102:105], v161 offset:24576
	ds_read_b128 v[106:109], v161 offset:28672
	ds_read_b128 v[110:113], v162
	ds_read_b128 v[206:209], v163 offset:16384
	ds_read_b128 v[210:213], v163 offset:20480
	ds_read_b128 v[214:217], v163 offset:24576
	ds_read_b128 v[218:221], v163 offset:28672
	ds_read_b128 v[222:225], v164
	ds_read_b128 v[226:229], v165 offset:16384
	ds_read_b128 v[230:233], v165 offset:20480
	ds_read_b128 v[234:237], v165 offset:24576
	ds_read_b128 v[238:241], v165 offset:28672
	s_waitcnt lgkmcnt(0)
	s_barrier
	s_mov_b32 m0, s36
	s_setprio 1
	v_mfma_f32_32x32x16_bf16 v[48:63], v[70:73], v[74:77], v[48:63]
	v_mfma_f32_32x32x16_bf16 v[32:47], v[70:73], v[78:81], v[32:47]
	global_load_lds_dwordx4 v254, s[18:19]
	s_add_u32 m0, m0, 0x1000
	v_mfma_f32_32x32x16_bf16 v[16:31], v[70:73], v[82:85], v[16:31]
	v_mfma_f32_32x32x16_bf16 v[0:15], v[70:73], v[86:89], v[0:15]
	global_load_lds_dwordx4 v254, s[20:21]
	s_add_u32 m0, m0, 0x1000
	v_mfma_f32_32x32x16_bf16 v[48:63], v[90:93], v[94:97], v[48:63]
	v_mfma_f32_32x32x16_bf16 v[32:47], v[90:93], v[98:101], v[32:47]
	global_load_lds_dwordx4 v254, s[22:23]
	s_add_u32 m0, m0, 0x1000
	v_mfma_f32_32x32x16_bf16 v[16:31], v[90:93], v[102:105], v[16:31]
	v_mfma_f32_32x32x16_bf16 v[0:15], v[90:93], v[106:109], v[0:15]
	global_load_lds_dwordx4 v254, s[24:25]
	s_add_u32 m0, m0, 0x1000
	v_mfma_f32_32x32x16_bf16 v[48:63], v[110:113], v[206:209], v[48:63]
	v_mfma_f32_32x32x16_bf16 v[32:47], v[110:113], v[210:213], v[32:47]
	global_load_lds_dwordx4 v254, s[26:27]
	s_add_u32 m0, m0, 0x1000
	v_mfma_f32_32x32x16_bf16 v[16:31], v[110:113], v[214:217], v[16:31]
	v_mfma_f32_32x32x16_bf16 v[0:15], v[110:113], v[218:221], v[0:15]
	global_load_lds_dwordx4 v254, s[28:29]
	s_add_u32 m0, m0, 0x1000
	v_mfma_f32_32x32x16_bf16 v[48:63], v[222:225], v[226:229], v[48:63]
	v_mfma_f32_32x32x16_bf16 v[32:47], v[222:225], v[230:233], v[32:47]
	global_load_lds_dwordx4 v254, s[30:31]
	s_add_u32 m0, m0, 0x1000
	v_mfma_f32_32x32x16_bf16 v[16:31], v[222:225], v[234:237], v[16:31]
	v_mfma_f32_32x32x16_bf16 v[0:15], v[222:225], v[238:241], v[0:15]
	global_load_lds_dwordx4 v254, s[34:35]
	s_setprio 0
	v_add_u32_e32 v254, 0x80, v254
	s_waitcnt vmcnt(8)
	s_barrier
	ds_read_b128 v[70:73], v158 offset:32768
	ds_read_b128 v[74:77], v159 offset:49152
	ds_read_b128 v[78:81], v159 offset:53248
	ds_read_b128 v[82:85], v159 offset:57344
	ds_read_b128 v[86:89], v159 offset:61440
	ds_read_b128 v[90:93], v160 offset:32768
	ds_read_b128 v[94:97], v161 offset:49152
	ds_read_b128 v[98:101], v161 offset:53248
	ds_read_b128 v[102:105], v161 offset:57344
	ds_read_b128 v[106:109], v161 offset:61440
	ds_read_b128 v[110:113], v162 offset:32768
	ds_read_b128 v[206:209], v163 offset:49152
	ds_read_b128 v[210:213], v163 offset:53248
	ds_read_b128 v[214:217], v163 offset:57344
	ds_read_b128 v[218:221], v163 offset:61440
	ds_read_b128 v[222:225], v164 offset:32768
	ds_read_b128 v[226:229], v165 offset:49152
	ds_read_b128 v[230:233], v165 offset:53248
	ds_read_b128 v[234:237], v165 offset:57344
	ds_read_b128 v[238:241], v165 offset:61440
	s_waitcnt lgkmcnt(0)
	s_barrier
	s_add_u32 m0, s36, 0x8000
	s_setprio 1
	v_mfma_f32_32x32x16_bf16 v[48:63], v[70:73], v[74:77], v[48:63]
	v_mfma_f32_32x32x16_bf16 v[32:47], v[70:73], v[78:81], v[32:47]
	global_load_lds_dwordx4 v254, s[18:19]
	s_add_u32 m0, m0, 0x1000
	v_mfma_f32_32x32x16_bf16 v[16:31], v[70:73], v[82:85], v[16:31]
	v_mfma_f32_32x32x16_bf16 v[0:15], v[70:73], v[86:89], v[0:15]
	global_load_lds_dwordx4 v254, s[20:21]
	s_add_u32 m0, m0, 0x1000
	v_mfma_f32_32x32x16_bf16 v[48:63], v[90:93], v[94:97], v[48:63]
	v_mfma_f32_32x32x16_bf16 v[32:47], v[90:93], v[98:101], v[32:47]
	global_load_lds_dwordx4 v254, s[22:23]
	s_add_u32 m0, m0, 0x1000
	v_mfma_f32_32x32x16_bf16 v[16:31], v[90:93], v[102:105], v[16:31]
	v_mfma_f32_32x32x16_bf16 v[0:15], v[90:93], v[106:109], v[0:15]
	global_load_lds_dwordx4 v254, s[24:25]
	s_add_u32 m0, m0, 0x1000
	v_mfma_f32_32x32x16_bf16 v[48:63], v[110:113], v[206:209], v[48:63]
	v_mfma_f32_32x32x16_bf16 v[32:47], v[110:113], v[210:213], v[32:47]
	global_load_lds_dwordx4 v254, s[26:27]
	s_add_u32 m0, m0, 0x1000
	v_mfma_f32_32x32x16_bf16 v[16:31], v[110:113], v[214:217], v[16:31]
	v_mfma_f32_32x32x16_bf16 v[0:15], v[110:113], v[218:221], v[0:15]
	global_load_lds_dwordx4 v254, s[28:29]
	s_add_u32 m0, m0, 0x1000
	v_mfma_f32_32x32x16_bf16 v[48:63], v[222:225], v[226:229], v[48:63]
	v_mfma_f32_32x32x16_bf16 v[32:47], v[222:225], v[230:233], v[32:47]
	global_load_lds_dwordx4 v254, s[30:31]
	s_add_u32 m0, m0, 0x1000
	v_mfma_f32_32x32x16_bf16 v[16:31], v[222:225], v[234:237], v[16:31]
	v_mfma_f32_32x32x16_bf16 v[0:15], v[222:225], v[238:241], v[0:15]
	global_load_lds_dwordx4 v254, s[34:35]
	s_setprio 0
	v_add_u32_e32 v254, 0x80, v254
	s_sub_u32 s37, s37, 1
	s_cmp_lg_u32 s37, 0
	s_cbranch_scc1 .Lgk_loop_p6
	s_add_u32 s40, s3, s33
	s_cmp_gt_u32 s40, 0x3ff
	s_cbranch_scc1 .Lgk_tailplain_p6
.LBB0_703_pf_p6:
	s_ashr_i32 s41, s40, 31
	s_lshr_b32 s41, s41, 26
	s_add_i32 s41, s40, s41
	s_ashr_i32 s42, s41, 6
	s_andn2_b32 s41, s41, 63
	s_sub_i32 s41, s40, s41
	s_ashr_i32 s43, s41, 31
	s_lshr_b32 s43, s43, 29
	s_add_i32 s43, s41, s43
	s_ashr_i32 s48, s43, 3
	s_and_b32 s43, s43, -8
	s_lshl_b32 s42, s42, 3
	s_sub_i32 s41, s41, s43
	s_add_i32 s41, s41, s42
	s_lshl_b32 s44, s41, 7
	s_ashr_i32 s45, s44, 31
	s_lshl_b32 s46, s48, 7
	s_lshl_b64 s[42:43], s[44:45], 11
	s_ashr_i32 s47, s46, 31
	s_lshl_b32 s38, s44, 11
	s_add_u32 s18, s14, s38
	s_addc_u32 s19, s15, 0
	s_add_u32 s18, s18, 0xb79f000
	s_addc_u32 s19, s19, 0
	s_add_u32 s20, s18, 0x10000
	s_addc_u32 s21, s19, 0
	s_add_u32 s22, s20, 0x10000
	s_addc_u32 s23, s21, 0
	s_add_u32 s24, s22, 0x10000
	s_addc_u32 s25, s23, 0
	s_lshl_b32 s38, s46, 11
	s_add_u32 s26, s14, s38
	s_addc_u32 s27, s15, 0
	s_add_u32 s26, s26, 0x3a0000
	s_addc_u32 s27, s27, 0
	s_add_u32 s28, s26, 0x10000
	s_addc_u32 s29, s27, 0
	s_add_u32 s30, s28, 0x10000
	s_addc_u32 s31, s29, 0
	s_add_u32 s34, s30, 0x10000
	s_addc_u32 s35, s31, 0
	v_mov_b32_e32 v254, v64
	s_mov_b32 s39, 1
	s_waitcnt vmcnt(8)
	s_barrier
	ds_read_b128 v[70:73], v158
	ds_read_b128 v[74:77], v159 offset:16384
	ds_read_b128 v[78:81], v159 offset:20480
	ds_read_b128 v[82:85], v159 offset:24576
	ds_read_b128 v[86:89], v159 offset:28672
	ds_read_b128 v[90:93], v160
	ds_read_b128 v[94:97], v161 offset:16384
	ds_read_b128 v[98:101], v161 offset:20480
	ds_read_b128 v[102:105], v161 offset:24576
	ds_read_b128 v[106:109], v161 offset:28672
	ds_read_b128 v[110:113], v162
	ds_read_b128 v[206:209], v163 offset:16384
	ds_read_b128 v[210:213], v163 offset:20480
	ds_read_b128 v[214:217], v163 offset:24576
	ds_read_b128 v[218:221], v163 offset:28672
	ds_read_b128 v[222:225], v164
	ds_read_b128 v[226:229], v165 offset:16384
	ds_read_b128 v[230:233], v165 offset:20480
	ds_read_b128 v[234:237], v165 offset:24576
	ds_read_b128 v[238:241], v165 offset:28672
	s_waitcnt lgkmcnt(0)
	s_barrier
	s_mov_b32 m0, s36
	s_setprio 1
	v_mfma_f32_32x32x16_bf16 v[48:63], v[70:73], v[74:77], v[48:63]
	v_mfma_f32_32x32x16_bf16 v[32:47], v[70:73], v[78:81], v[32:47]
	global_load_lds_dwordx4 v254, s[18:19]
	s_add_u32 m0, m0, 0x1000
	v_mfma_f32_32x32x16_bf16 v[16:31], v[70:73], v[82:85], v[16:31]
	v_mfma_f32_32x32x16_bf16 v[0:15], v[70:73], v[86:89], v[0:15]
	global_load_lds_dwordx4 v254, s[20:21]
	s_add_u32 m0, m0, 0x1000
	v_mfma_f32_32x32x16_bf16 v[48:63], v[90:93], v[94:97], v[48:63]
	v_mfma_f32_32x32x16_bf16 v[32:47], v[90:93], v[98:101], v[32:47]
	global_load_lds_dwordx4 v254, s[22:23]
	s_add_u32 m0, m0, 0x1000
	v_mfma_f32_32x32x16_bf16 v[16:31], v[90:93], v[102:105], v[16:31]
	v_mfma_f32_32x32x16_bf16 v[0:15], v[90:93], v[106:109], v[0:15]
	global_load_lds_dwordx4 v254, s[24:25]
	s_add_u32 m0, m0, 0x1000
	v_mfma_f32_32x32x16_bf16 v[48:63], v[110:113], v[206:209], v[48:63]
	v_mfma_f32_32x32x16_bf16 v[32:47], v[110:113], v[210:213], v[32:47]
	global_load_lds_dwordx4 v254, s[26:27]
	s_add_u32 m0, m0, 0x1000
	v_mfma_f32_32x32x16_bf16 v[16:31], v[110:113], v[214:217], v[16:31]
	v_mfma_f32_32x32x16_bf16 v[0:15], v[110:113], v[218:221], v[0:15]
	global_load_lds_dwordx4 v254, s[28:29]
	s_add_u32 m0, m0, 0x1000
	v_mfma_f32_32x32x16_bf16 v[48:63], v[222:225], v[226:229], v[48:63]
	v_mfma_f32_32x32x16_bf16 v[32:47], v[222:225], v[230:233], v[32:47]
	global_load_lds_dwordx4 v254, s[30:31]
	s_add_u32 m0, m0, 0x1000
	v_mfma_f32_32x32x16_bf16 v[16:31], v[222:225], v[234:237], v[16:31]
	v_mfma_f32_32x32x16_bf16 v[0:15], v[222:225], v[238:241], v[0:15]
	global_load_lds_dwordx4 v254, s[34:35]
	s_setprio 0
	v_add_u32_e32 v254, 0x80, v254
	s_waitcnt vmcnt(8)
	s_barrier
	ds_read_b128 v[70:73], v158 offset:32768
	ds_read_b128 v[74:77], v159 offset:49152
	ds_read_b128 v[78:81], v159 offset:53248
	ds_read_b128 v[82:85], v159 offset:57344
	ds_read_b128 v[86:89], v159 offset:61440
	ds_read_b128 v[90:93], v160 offset:32768
	ds_read_b128 v[94:97], v161 offset:49152
	ds_read_b128 v[98:101], v161 offset:53248
	ds_read_b128 v[102:105], v161 offset:57344
	ds_read_b128 v[106:109], v161 offset:61440
	ds_read_b128 v[110:113], v162 offset:32768
	ds_read_b128 v[206:209], v163 offset:49152
	ds_read_b128 v[210:213], v163 offset:53248
	ds_read_b128 v[214:217], v163 offset:57344
	ds_read_b128 v[218:221], v163 offset:61440
	ds_read_b128 v[222:225], v164 offset:32768
	ds_read_b128 v[226:229], v165 offset:49152
	ds_read_b128 v[230:233], v165 offset:53248
	ds_read_b128 v[234:237], v165 offset:57344
	ds_read_b128 v[238:241], v165 offset:61440
	s_waitcnt lgkmcnt(0)
	s_barrier
	s_add_u32 m0, s36, 0x8000
	s_setprio 1
	v_mfma_f32_32x32x16_bf16 v[48:63], v[70:73], v[74:77], v[48:63]
	v_mfma_f32_32x32x16_bf16 v[32:47], v[70:73], v[78:81], v[32:47]
	global_load_lds_dwordx4 v254, s[18:19]
	s_add_u32 m0, m0, 0x1000
	v_mfma_f32_32x32x16_bf16 v[16:31], v[70:73], v[82:85], v[16:31]
	v_mfma_f32_32x32x16_bf16 v[0:15], v[70:73], v[86:89], v[0:15]
	global_load_lds_dwordx4 v254, s[20:21]
	s_add_u32 m0, m0, 0x1000
	v_mfma_f32_32x32x16_bf16 v[48:63], v[90:93], v[94:97], v[48:63]
	v_mfma_f32_32x32x16_bf16 v[32:47], v[90:93], v[98:101], v[32:47]
	global_load_lds_dwordx4 v254, s[22:23]
	s_add_u32 m0, m0, 0x1000
	v_mfma_f32_32x32x16_bf16 v[16:31], v[90:93], v[102:105], v[16:31]
	v_mfma_f32_32x32x16_bf16 v[0:15], v[90:93], v[106:109], v[0:15]
	global_load_lds_dwordx4 v254, s[24:25]
	s_add_u32 m0, m0, 0x1000
	v_mfma_f32_32x32x16_bf16 v[48:63], v[110:113], v[206:209], v[48:63]
	v_mfma_f32_32x32x16_bf16 v[32:47], v[110:113], v[210:213], v[32:47]
	global_load_lds_dwordx4 v254, s[26:27]
	s_add_u32 m0, m0, 0x1000
	v_mfma_f32_32x32x16_bf16 v[16:31], v[110:113], v[214:217], v[16:31]
	v_mfma_f32_32x32x16_bf16 v[0:15], v[110:113], v[218:221], v[0:15]
	global_load_lds_dwordx4 v254, s[28:29]
	s_add_u32 m0, m0, 0x1000
	v_mfma_f32_32x32x16_bf16 v[48:63], v[222:225], v[226:229], v[48:63]
	v_mfma_f32_32x32x16_bf16 v[32:47], v[222:225], v[230:233], v[32:47]
	global_load_lds_dwordx4 v254, s[30:31]
	s_add_u32 m0, m0, 0x1000
	v_mfma_f32_32x32x16_bf16 v[16:31], v[222:225], v[234:237], v[16:31]
	v_mfma_f32_32x32x16_bf16 v[0:15], v[222:225], v[238:241], v[0:15]
	global_load_lds_dwordx4 v254, s[34:35]
	s_setprio 0
	v_add_u32_e32 v254, 0x80, v254
	s_branch .LBB0_707
.Lgk_tailplain_p6:
	s_mov_b32 s39, 0
	s_waitcnt vmcnt(8)
	s_barrier
	ds_read_b128 v[70:73], v158
	ds_read_b128 v[74:77], v159 offset:16384
	ds_read_b128 v[78:81], v159 offset:20480
	ds_read_b128 v[82:85], v159 offset:24576
	ds_read_b128 v[86:89], v159 offset:28672
	ds_read_b128 v[90:93], v160
	ds_read_b128 v[94:97], v161 offset:16384
	ds_read_b128 v[98:101], v161 offset:20480
	ds_read_b128 v[102:105], v161 offset:24576
	ds_read_b128 v[106:109], v161 offset:28672
	ds_read_b128 v[110:113], v162
	ds_read_b128 v[206:209], v163 offset:16384
	ds_read_b128 v[210:213], v163 offset:20480
	ds_read_b128 v[214:217], v163 offset:24576
	ds_read_b128 v[218:221], v163 offset:28672
	ds_read_b128 v[222:225], v164
	ds_read_b128 v[226:229], v165 offset:16384
	ds_read_b128 v[230:233], v165 offset:20480
	ds_read_b128 v[234:237], v165 offset:24576
	ds_read_b128 v[238:241], v165 offset:28672
	s_waitcnt lgkmcnt(0)
	s_barrier
	s_setprio 1
	v_mfma_f32_32x32x16_bf16 v[48:63], v[70:73], v[74:77], v[48:63]
	v_mfma_f32_32x32x16_bf16 v[32:47], v[70:73], v[78:81], v[32:47]
	v_mfma_f32_32x32x16_bf16 v[16:31], v[70:73], v[82:85], v[16:31]
	v_mfma_f32_32x32x16_bf16 v[0:15], v[70:73], v[86:89], v[0:15]
	v_mfma_f32_32x32x16_bf16 v[48:63], v[90:93], v[94:97], v[48:63]
	v_mfma_f32_32x32x16_bf16 v[32:47], v[90:93], v[98:101], v[32:47]
	v_mfma_f32_32x32x16_bf16 v[16:31], v[90:93], v[102:105], v[16:31]
	v_mfma_f32_32x32x16_bf16 v[0:15], v[90:93], v[106:109], v[0:15]
	v_mfma_f32_32x32x16_bf16 v[48:63], v[110:113], v[206:209], v[48:63]
	v_mfma_f32_32x32x16_bf16 v[32:47], v[110:113], v[210:213], v[32:47]
	v_mfma_f32_32x32x16_bf16 v[16:31], v[110:113], v[214:217], v[16:31]
	v_mfma_f32_32x32x16_bf16 v[0:15], v[110:113], v[218:221], v[0:15]
	v_mfma_f32_32x32x16_bf16 v[48:63], v[222:225], v[226:229], v[48:63]
	v_mfma_f32_32x32x16_bf16 v[32:47], v[222:225], v[230:233], v[32:47]
	v_mfma_f32_32x32x16_bf16 v[16:31], v[222:225], v[234:237], v[16:31]
	v_mfma_f32_32x32x16_bf16 v[0:15], v[222:225], v[238:241], v[0:15]
	s_setprio 0
	s_waitcnt vmcnt(0)
	s_barrier
	ds_read_b128 v[70:73], v158 offset:32768
	ds_read_b128 v[74:77], v159 offset:49152
	ds_read_b128 v[78:81], v159 offset:53248
	ds_read_b128 v[82:85], v159 offset:57344
	ds_read_b128 v[86:89], v159 offset:61440
	ds_read_b128 v[90:93], v160 offset:32768
	ds_read_b128 v[94:97], v161 offset:49152
	ds_read_b128 v[98:101], v161 offset:53248
	ds_read_b128 v[102:105], v161 offset:57344
	ds_read_b128 v[106:109], v161 offset:61440
	ds_read_b128 v[110:113], v162 offset:32768
	ds_read_b128 v[206:209], v163 offset:49152
	ds_read_b128 v[210:213], v163 offset:53248
	ds_read_b128 v[214:217], v163 offset:57344
	ds_read_b128 v[218:221], v163 offset:61440
	ds_read_b128 v[222:225], v164 offset:32768
	ds_read_b128 v[226:229], v165 offset:49152
	ds_read_b128 v[230:233], v165 offset:53248
	ds_read_b128 v[234:237], v165 offset:57344
	ds_read_b128 v[238:241], v165 offset:61440
	s_waitcnt lgkmcnt(0)
	s_barrier
	s_setprio 1
	v_mfma_f32_32x32x16_bf16 v[48:63], v[70:73], v[74:77], v[48:63]
	v_mfma_f32_32x32x16_bf16 v[32:47], v[70:73], v[78:81], v[32:47]
	v_mfma_f32_32x32x16_bf16 v[16:31], v[70:73], v[82:85], v[16:31]
	v_mfma_f32_32x32x16_bf16 v[0:15], v[70:73], v[86:89], v[0:15]
	v_mfma_f32_32x32x16_bf16 v[48:63], v[90:93], v[94:97], v[48:63]
	v_mfma_f32_32x32x16_bf16 v[32:47], v[90:93], v[98:101], v[32:47]
	v_mfma_f32_32x32x16_bf16 v[16:31], v[90:93], v[102:105], v[16:31]
	v_mfma_f32_32x32x16_bf16 v[0:15], v[90:93], v[106:109], v[0:15]
	v_mfma_f32_32x32x16_bf16 v[48:63], v[110:113], v[206:209], v[48:63]
	v_mfma_f32_32x32x16_bf16 v[32:47], v[110:113], v[210:213], v[32:47]
	v_mfma_f32_32x32x16_bf16 v[16:31], v[110:113], v[214:217], v[16:31]
	v_mfma_f32_32x32x16_bf16 v[0:15], v[110:113], v[218:221], v[0:15]
	v_mfma_f32_32x32x16_bf16 v[48:63], v[222:225], v[226:229], v[48:63]
	v_mfma_f32_32x32x16_bf16 v[32:47], v[222:225], v[230:233], v[32:47]
	v_mfma_f32_32x32x16_bf16 v[16:31], v[222:225], v[234:237], v[16:31]
	v_mfma_f32_32x32x16_bf16 v[0:15], v[222:225], v[238:241], v[0:15]
	s_setprio 0
	s_branch .LBB0_707
.LBB0_707:
	s_add_i32 s58, s64, 0xffffe000
	s_lshr_b32 s58, s58, 12
	s_mulk_i32 s58, 0x1800
	s_addk_i32 s58, 0x1800
	s_cmp_gt_i32 s6, 63
	s_cselect_b32 s6, s58, 0
	s_lshl_b64 s[58:59], s[6:7], 2
	v_mov_b32_e32 v70, s68
	s_add_u32 s6, s14, s58
	ds_read_b64 v[70:71], v70
	s_addc_u32 s63, s15, s59
	s_lshl_b32 s58, s69, 14
	s_add_i32 s58, s58, 0x20000
	s_ashr_i32 s59, s58, 31
	s_lshl_b64 s[58:59], s[58:59], 2
	s_add_u32 s58, s10, s58
	s_waitcnt lgkmcnt(0)
	v_readfirstlane_b32 s70, v70
	s_addc_u32 s59, s11, s59
	v_add_u32_e32 v70, s64, v141
	s_add_u32 s60, s6, 0x5ba2000
	v_lshlrev_b32_e32 v190, 10, v70
	s_addc_u32 s61, s63, 0
	v_or_b32_e32 v102, s66, v140
	v_or_b32_e32 v188, 0x400, v190
	v_or_b32_e32 v187, 0x4400, v190
	v_or_b32_e32 v191, 0x4c00, v190
	v_or_b32_e32 v195, 0x6c00, v190
	v_readfirstlane_b32 s71, v71
	s_add_u32 s62, s6, 0x5ba4000
	v_ashrrev_i32_e32 v103, 31, v102
	v_add_u32_e32 v134, v190, v102
	v_add_u32_e32 v136, v188, v102
	v_or_b32_e32 v186, 0x800, v190
	v_or_b32_e32 v185, 0xc00, v190
	v_or_b32_e32 v183, 0x2000, v190
	v_or_b32_e32 v181, 0x2400, v190
	v_or_b32_e32 v71, 0x2800, v190
	v_or_b32_e32 v182, 0x2c00, v190
	v_or_b32_e32 v184, 0x4000, v190
	v_add_u32_e32 v114, v187, v102
	v_or_b32_e32 v189, 0x4800, v190
	v_add_u32_e32 v120, v191, v102
	v_or_b32_e32 v192, 0x6000, v190
	v_or_b32_e32 v193, 0x6400, v190
	v_or_b32_e32 v194, 0x6800, v190
	v_add_u32_e32 v130, v195, v102
	s_addc_u32 s63, s63, 0
	v_lshlrev_b64 v[72:73], 2, v[102:103]
	v_ashrrev_i32_e32 v137, 31, v136
	v_add_u32_e32 v138, v186, v102
	v_add_u32_e32 v132, v185, v102
	v_add_u32_e32 v124, v183, v102
	v_add_u32_e32 v116, v181, v102
	v_add_u32_e32 v108, v71, v102
	v_add_u32_e32 v110, v182, v102
	v_add_u32_e32 v112, v184, v102
	v_ashrrev_i32_e32 v115, 31, v114
	v_add_u32_e32 v118, v189, v102
	v_ashrrev_i32_e32 v121, 31, v120
	v_add_u32_e32 v122, v192, v102
	v_add_u32_e32 v126, v193, v102
	v_add_u32_e32 v128, v194, v102
	v_ashrrev_i32_e32 v131, 31, v130
	v_ashrrev_i32_e32 v135, 31, v134
	v_lshl_add_u64 v[74:75], s[60:61], 0, v[72:73]
	v_lshl_add_u64 v[104:105], s[70:71], 0, v[72:73]
	v_lshl_add_u64 v[72:73], s[62:63], 0, v[72:73]
	v_lshl_add_u64 v[88:89], v[136:137], 2, s[12:13]
	v_ashrrev_i32_e32 v139, 31, v138
	v_ashrrev_i32_e32 v133, 31, v132
	v_ashrrev_i32_e32 v125, 31, v124
	v_ashrrev_i32_e32 v117, 31, v116
	v_ashrrev_i32_e32 v109, 31, v108
	v_ashrrev_i32_e32 v111, 31, v110
	v_ashrrev_i32_e32 v113, 31, v112
	v_lshl_add_u64 v[86:87], v[114:115], 2, s[12:13]
	v_ashrrev_i32_e32 v119, 31, v118
	v_lshl_add_u64 v[92:93], v[120:121], 2, s[12:13]
	v_ashrrev_i32_e32 v123, 31, v122
	v_ashrrev_i32_e32 v127, 31, v126
	v_ashrrev_i32_e32 v129, 31, v128
	v_lshl_add_u64 v[100:101], v[130:131], 2, s[12:13]
	v_lshl_add_u64 v[106:107], v[134:135], 2, s[12:13]
	global_load_dword v196, v[74:75], off
	global_load_dword v198, v[72:73], off
	global_load_dword v197, v[104:105], off
	v_lshl_add_u64 v[84:85], v[138:139], 2, s[12:13]
	v_lshl_add_u64 v[82:83], v[132:133], 2, s[12:13]
	v_lshl_add_u64 v[78:79], v[124:125], 2, s[12:13]
	v_lshl_add_u64 v[72:73], v[116:117], 2, s[12:13]
	v_lshl_add_u64 v[74:75], v[108:109], 2, s[12:13]
	v_lshl_add_u64 v[76:77], v[110:111], 2, s[12:13]
	v_lshl_add_u64 v[80:81], v[112:113], 2, s[12:13]
	global_load_dword v180, v[88:89], off
	global_load_dword v179, v[84:85], off
	global_load_dword v178, v[82:83], off
	global_load_dword v177, v[78:79], off
	global_load_dword v176, v[72:73], off
	global_load_dword v175, v[74:75], off
	global_load_dword v174, v[76:77], off
	global_load_dword v173, v[80:81], off
	v_lshl_add_u64 v[90:91], v[118:119], 2, s[12:13]
	global_load_dword v172, v[86:87], off
	global_load_dword v170, v[90:91], off
	v_lshl_add_u64 v[94:95], v[122:123], 2, s[12:13]
	v_lshl_add_u64 v[96:97], v[126:127], 2, s[12:13]
	v_lshl_add_u64 v[98:99], v[128:129], 2, s[12:13]
	global_load_dword v171, v[92:93], off
	global_load_dword v169, v[94:95], off
	global_load_dword v168, v[96:97], off
	global_load_dword v167, v[98:99], off
	global_load_dword v103, v[100:101], off
	global_load_dword v202, v[106:107], off
	v_lshl_add_u64 v[108:109], v[108:109], 1, s[8:9]
	s_waitcnt vmcnt(0)
	v_add_f32_e32 v198, 1.0, v198
	v_mul_f32_e32 v197, v197, v198
	v_fmac_f32_e32 v180, v49, v196
	v_fmac_f32_e32 v179, v50, v196
	v_fmac_f32_e32 v178, v51, v196
	v_fmac_f32_e32 v177, v52, v196
	v_fmac_f32_e32 v176, v53, v196
	v_fmac_f32_e32 v175, v54, v196
	v_fmac_f32_e32 v174, v55, v196
	v_fmac_f32_e32 v173, v56, v196
	v_fmac_f32_e32 v172, v57, v196
	v_fmac_f32_e32 v170, v58, v196
	v_fmac_f32_e32 v171, v59, v196
	v_fmac_f32_e32 v169, v60, v196
	v_fmac_f32_e32 v168, v61, v196
	v_fmac_f32_e32 v167, v62, v196
	v_fmac_f32_e32 v103, v63, v196
	v_fmac_f32_e32 v202, v48, v196
	v_or_b32_e32 v48, 32, v102
	v_ashrrev_i32_e32 v49, 31, v48
	v_lshlrev_b64 v[50:51], 2, v[48:49]
	global_store_dword v[88:89], v180, off sc1
	global_store_dword v[84:85], v179, off sc1
	global_store_dword v[82:83], v178, off sc1
	global_store_dword v[78:79], v177, off sc1
	global_store_dword v[72:73], v176, off sc1
	global_store_dword v[74:75], v175, off sc1
	global_store_dword v[76:77], v174, off sc1
	global_store_dword v[80:81], v173, off sc1
	global_store_dword v[86:87], v172, off sc1
	global_store_dword v[90:91], v170, off sc1
	global_store_dword v[92:93], v171, off sc1
	global_store_dword v[94:95], v169, off sc1
	global_store_dword v[96:97], v168, off sc1
	global_store_dword v[98:99], v167, off sc1
	global_store_dword v[100:101], v103, off sc1
	global_store_dword v[106:107], v202, off sc1
	v_mul_f32_e32 v54, v197, v202
	v_lshl_add_u64 v[52:53], s[60:61], 0, v[50:51]
	v_lshl_add_u64 v[50:51], s[62:63], 0, v[50:51]
	global_load_dword v198, v[106:107], off offset:128
	global_load_dword v196, v[52:53], off
	global_load_dword v203, v[50:51], off
	global_load_dword v204, v[104:105], off offset:128
	v_cvt_pk_bf16_f32 v49, v54, s0
	v_lshl_add_u64 v[50:51], v[134:135], 1, s[8:9]
	global_store_short v[50:51], v49, off sc1
	v_mul_f32_e32 v49, v197, v180
	v_cvt_pk_bf16_f32 v49, v49, s0
	v_lshl_add_u64 v[50:51], v[136:137], 1, s[8:9]
	global_store_short v[50:51], v49, off sc1
	v_mul_f32_e32 v49, v197, v179
	v_cvt_pk_bf16_f32 v49, v49, s0
	v_lshl_add_u64 v[50:51], v[138:139], 1, s[8:9]
	global_store_short v[50:51], v49, off sc1
	v_mul_f32_e32 v49, v197, v178
	v_cvt_pk_bf16_f32 v49, v49, s0
	v_lshl_add_u64 v[50:51], v[132:133], 1, s[8:9]
	global_store_short v[50:51], v49, off sc1
	v_mul_f32_e32 v49, v197, v177
	v_cvt_pk_bf16_f32 v49, v49, s0
	v_lshl_add_u64 v[50:51], v[124:125], 1, s[8:9]
	global_store_short v[50:51], v49, off sc1
	v_mul_f32_e32 v49, v197, v176
	v_cvt_pk_bf16_f32 v49, v49, s0
	v_lshl_add_u64 v[50:51], v[116:117], 1, s[8:9]
	global_store_short v[50:51], v49, off sc1
	v_mul_f32_e32 v49, v197, v175
	global_load_dword v62, v[84:85], off offset:128
	global_load_dword v60, v[78:79], off offset:128
	global_load_dword v59, v[72:73], off offset:128
	global_load_dword v58, v[74:75], off offset:128
	global_load_dword v56, v[80:81], off offset:128
	global_load_dword v57, v[76:77], off offset:128
	global_load_dword v55, v[86:87], off offset:128
	global_load_dword v61, v[82:83], off offset:128
	global_load_dword v54, v[90:91], off offset:128
	global_load_dword v53, v[92:93], off offset:128
	global_load_dword v52, v[94:95], off offset:128
	global_load_dword v51, v[96:97], off offset:128
	global_load_dword v50, v[98:99], off offset:128
	v_cvt_pk_bf16_f32 v63, v49, s0
	global_load_dword v49, v[100:101], off offset:128
	s_waitcnt vmcnt(22)
	v_fmac_f32_e32 v198, v32, v196
	global_store_short v[108:109], v63, off sc1
	global_load_dword v63, v[88:89], off offset:128
	v_mul_f32_e32 v108, v197, v174
	v_cvt_pk_bf16_f32 v116, v108, s0
	v_lshl_add_u64 v[108:109], v[110:111], 1, s[8:9]
	global_store_short v[108:109], v116, off sc1
	v_mul_f32_e32 v108, v197, v173
	v_cvt_pk_bf16_f32 v110, v108, s0
	v_lshl_add_u64 v[108:109], v[112:113], 1, s[8:9]
	global_store_short v[108:109], v110, off sc1
	v_mul_f32_e32 v108, v197, v172
	v_cvt_pk_bf16_f32 v110, v108, s0
	v_lshl_add_u64 v[108:109], v[114:115], 1, s[8:9]
	global_store_short v[108:109], v110, off sc1
	v_mul_f32_e32 v108, v197, v170
	v_cvt_pk_bf16_f32 v110, v108, s0
	v_lshl_add_u64 v[108:109], v[118:119], 1, s[8:9]
	global_store_short v[108:109], v110, off sc1
	v_mul_f32_e32 v108, v197, v171
	v_cvt_pk_bf16_f32 v110, v108, s0
	v_lshl_add_u64 v[108:109], v[120:121], 1, s[8:9]
	global_store_short v[108:109], v110, off sc1
	v_mul_f32_e32 v108, v197, v169
	v_cvt_pk_bf16_f32 v110, v108, s0
	v_lshl_add_u64 v[108:109], v[122:123], 1, s[8:9]
	global_store_short v[108:109], v110, off sc1
	v_mul_f32_e32 v108, v197, v168
	v_cvt_pk_bf16_f32 v110, v108, s0
	v_lshl_add_u64 v[108:109], v[126:127], 1, s[8:9]
	global_store_short v[108:109], v110, off sc1
	v_mul_f32_e32 v108, v197, v167
	v_cvt_pk_bf16_f32 v110, v108, s0
	v_lshl_add_u64 v[108:109], v[128:129], 1, s[8:9]
	global_store_short v[108:109], v110, off sc1
	v_mul_f32_e32 v108, v197, v103
	v_cvt_pk_bf16_f32 v110, v108, s0
	v_lshl_add_u64 v[108:109], v[130:131], 1, s[8:9]
	global_store_short v[108:109], v110, off sc1
	s_waitcnt vmcnt(32)
	v_add_f32_e32 v108, 1.0, v203
	s_waitcnt vmcnt(31)
	v_mul_f32_e32 v112, v204, v108
	v_add_u32_e32 v108, v190, v48
	s_waitcnt vmcnt(24)
	v_fmac_f32_e32 v62, v34, v196
	s_waitcnt vmcnt(17)
	v_fmac_f32_e32 v61, v35, v196
	v_fmac_f32_e32 v60, v36, v196
	v_fmac_f32_e32 v59, v37, v196
	v_fmac_f32_e32 v58, v38, v196
	v_fmac_f32_e32 v57, v39, v196
	v_fmac_f32_e32 v56, v40, v196
	v_fmac_f32_e32 v55, v41, v196
	s_waitcnt vmcnt(16)
	v_fmac_f32_e32 v54, v42, v196
	s_waitcnt vmcnt(15)
	v_fmac_f32_e32 v53, v43, v196
	s_waitcnt vmcnt(14)
	v_fmac_f32_e32 v52, v44, v196
	s_waitcnt vmcnt(13)
	v_fmac_f32_e32 v51, v45, v196
	s_waitcnt vmcnt(12)
	v_fmac_f32_e32 v50, v46, v196
	s_waitcnt vmcnt(11)
	v_fmac_f32_e32 v49, v47, v196
	v_ashrrev_i32_e32 v109, 31, v108
	global_store_dword v[106:107], v198, off offset:128 sc1
	v_mul_f32_e32 v32, v112, v198
	global_store_dword v[84:85], v62, off offset:128 sc1
	global_store_dword v[82:83], v61, off offset:128 sc1
	global_store_dword v[78:79], v60, off offset:128 sc1
	global_store_dword v[72:73], v59, off offset:128 sc1
	global_store_dword v[74:75], v58, off offset:128 sc1
	global_store_dword v[76:77], v57, off offset:128 sc1
	global_store_dword v[80:81], v56, off offset:128 sc1
	global_store_dword v[86:87], v55, off offset:128 sc1
	global_store_dword v[90:91], v54, off offset:128 sc1
	global_store_dword v[92:93], v53, off offset:128 sc1
	global_store_dword v[94:95], v52, off offset:128 sc1
	global_store_dword v[96:97], v51, off offset:128 sc1
	global_store_dword v[98:99], v50, off offset:128 sc1
	global_store_dword v[100:101], v49, off offset:128 sc1
	v_cvt_pk_bf16_f32 v32, v32, s0
	v_lshl_add_u64 v[108:109], v[108:109], 1, s[8:9]
	v_add_u32_e32 v110, v188, v48
	global_load_dword v45, v[88:89], off offset:256
	v_ashrrev_i32_e32 v111, 31, v110
	global_store_short v[108:109], v32, off sc1
	v_mul_f32_e32 v40, v112, v59
	v_mul_f32_e32 v115, v112, v56
	v_cvt_pk_bf16_f32 v115, v115, s0
	s_waitcnt vmcnt(26)
	v_fmac_f32_e32 v63, v33, v196
	v_mul_f32_e32 v32, v112, v63
	v_cvt_pk_bf16_f32 v34, v32, s0
	v_lshl_add_u64 v[32:33], v[110:111], 1, s[8:9]
	global_store_short v[32:33], v34, off sc1
	v_add_u32_e32 v32, v186, v48
	v_ashrrev_i32_e32 v33, 31, v32
	v_mul_f32_e32 v34, v112, v62
	v_cvt_pk_bf16_f32 v34, v34, s0
	v_lshl_add_u64 v[32:33], v[32:33], 1, s[8:9]
	global_store_short v[32:33], v34, off sc1
	v_add_u32_e32 v32, v185, v48
	v_ashrrev_i32_e32 v33, 31, v32
	v_mul_f32_e32 v34, v112, v61
	v_cvt_pk_bf16_f32 v34, v34, s0
	v_lshl_add_u64 v[32:33], v[32:33], 1, s[8:9]
	global_store_short v[32:33], v34, off sc1
	v_add_u32_e32 v32, v183, v48
	v_ashrrev_i32_e32 v33, 31, v32
	v_mul_f32_e32 v34, v112, v60
	v_cvt_pk_bf16_f32 v34, v34, s0
	v_lshl_add_u64 v[32:33], v[32:33], 1, s[8:9]
	global_store_short v[32:33], v34, off sc1
	v_or_b32_e32 v32, 64, v102
	v_add_u32_e32 v34, v181, v48
	v_ashrrev_i32_e32 v33, 31, v32
	v_ashrrev_i32_e32 v35, 31, v34
	v_lshlrev_b64 v[36:37], 2, v[32:33]
	global_store_dword v[88:89], v63, off offset:128 sc1
	v_lshl_add_u64 v[38:39], s[60:61], 0, v[36:37]
	v_cvt_pk_bf16_f32 v33, v40, s0
	v_lshl_add_u64 v[34:35], v[34:35], 1, s[8:9]
	v_lshl_add_u64 v[36:37], s[62:63], 0, v[36:37]
	global_load_dword v109, v[38:39], off
	global_load_dword v113, v[36:37], off
	global_load_dword v114, v[104:105], off offset:256
	global_load_dword v116, v[106:107], off offset:256
	global_load_dword v47, v[84:85], off offset:256
	global_load_dword v44, v[78:79], off offset:256
	global_load_dword v39, v[86:87], off offset:256
	global_load_dword v46, v[82:83], off offset:256
	global_load_dword v43, v[72:73], off offset:256
	global_load_dword v42, v[74:75], off offset:256
	global_load_dword v40, v[80:81], off offset:256
	global_load_dword v41, v[76:77], off offset:256
	global_load_dword v38, v[90:91], off offset:256
	global_load_dword v37, v[92:93], off offset:256
	global_load_dword v36, v[94:95], off offset:256
	v_add_u32_e32 v110, v184, v48
	global_store_short v[34:35], v33, off sc1
	v_add_u32_e32 v34, v71, v48
	v_ashrrev_i32_e32 v35, 31, v34
	v_mul_f32_e32 v33, v112, v58
	v_cvt_pk_bf16_f32 v33, v33, s0
	v_lshl_add_u64 v[34:35], v[34:35], 1, s[8:9]
	global_store_short v[34:35], v33, off sc1
	v_add_u32_e32 v34, v182, v48
	v_ashrrev_i32_e32 v35, 31, v34
	v_mul_f32_e32 v33, v112, v57
	v_cvt_pk_bf16_f32 v33, v33, s0
	v_lshl_add_u64 v[34:35], v[34:35], 1, s[8:9]
	global_store_short v[34:35], v33, off sc1
	global_load_dword v35, v[96:97], off offset:256
	v_ashrrev_i32_e32 v111, 31, v110
	global_load_dword v34, v[98:99], off offset:256
	global_load_dword v33, v[100:101], off offset:256
	v_lshl_add_u64 v[110:111], v[110:111], 1, s[8:9]
	global_store_short v[110:111], v115, off sc1
	v_add_u32_e32 v110, v187, v48
	v_ashrrev_i32_e32 v111, 31, v110
	v_mul_f32_e32 v115, v112, v55
	v_cvt_pk_bf16_f32 v115, v115, s0
	v_lshl_add_u64 v[110:111], v[110:111], 1, s[8:9]
	global_store_short v[110:111], v115, off sc1
	v_add_u32_e32 v110, v189, v48
	v_ashrrev_i32_e32 v111, 31, v110
	v_mul_f32_e32 v115, v112, v54
	v_cvt_pk_bf16_f32 v115, v115, s0
	v_lshl_add_u64 v[110:111], v[110:111], 1, s[8:9]
	global_store_short v[110:111], v115, off sc1
	v_add_u32_e32 v110, v191, v48
	v_ashrrev_i32_e32 v111, 31, v110
	v_mul_f32_e32 v115, v112, v53
	v_cvt_pk_bf16_f32 v115, v115, s0
	v_lshl_add_u64 v[110:111], v[110:111], 1, s[8:9]
	global_store_short v[110:111], v115, off sc1
	v_add_u32_e32 v110, v192, v48
	v_ashrrev_i32_e32 v111, 31, v110
	v_mul_f32_e32 v115, v112, v52
	v_cvt_pk_bf16_f32 v115, v115, s0
	v_lshl_add_u64 v[110:111], v[110:111], 1, s[8:9]
	global_store_short v[110:111], v115, off sc1
	v_add_u32_e32 v110, v193, v48
	v_ashrrev_i32_e32 v111, 31, v110
	v_mul_f32_e32 v115, v112, v51
	v_cvt_pk_bf16_f32 v115, v115, s0
	v_lshl_add_u64 v[110:111], v[110:111], 1, s[8:9]
	global_store_short v[110:111], v115, off sc1
	v_add_u32_e32 v110, v194, v48
	v_ashrrev_i32_e32 v111, 31, v110
	v_mul_f32_e32 v115, v112, v50
	v_cvt_pk_bf16_f32 v115, v115, s0
	v_lshl_add_u64 v[110:111], v[110:111], 1, s[8:9]
	global_store_short v[110:111], v115, off sc1
	v_add_u32_e32 v110, v195, v48
	v_ashrrev_i32_e32 v111, 31, v110
	v_mul_f32_e32 v48, v112, v49
	v_cvt_pk_bf16_f32 v48, v48, s0
	v_lshl_add_u64 v[110:111], v[110:111], 1, s[8:9]
	global_store_short v[110:111], v48, off sc1
	v_add_u32_e32 v110, v190, v32
	v_ashrrev_i32_e32 v111, 31, v110
	v_mul_f32_e32 v108, v198, v198
	s_waitcnt vmcnt(28)
	v_fmac_f32_e32 v45, v17, v109
	s_waitcnt vmcnt(27)
	v_add_f32_e32 v48, 1.0, v113
	s_waitcnt vmcnt(26)
	v_mul_f32_e32 v48, v114, v48
	s_waitcnt vmcnt(25)
	v_fmac_f32_e32 v116, v16, v109
	v_mul_f32_e32 v16, v48, v116
	s_waitcnt vmcnt(24)
	v_fmac_f32_e32 v47, v18, v109
	v_cvt_pk_bf16_f32 v18, v16, s0
	v_lshl_add_u64 v[16:17], v[110:111], 1, s[8:9]
	global_store_short v[16:17], v18, off sc1
	v_add_u32_e32 v16, v188, v32
	v_ashrrev_i32_e32 v17, 31, v16
	v_mul_f32_e32 v18, v48, v45
	v_cvt_pk_bf16_f32 v18, v18, s0
	v_lshl_add_u64 v[16:17], v[16:17], 1, s[8:9]
	global_store_short v[16:17], v18, off sc1
	v_add_u32_e32 v16, v186, v32
	v_ashrrev_i32_e32 v17, 31, v16
	v_mul_f32_e32 v18, v48, v47
	v_cvt_pk_bf16_f32 v18, v18, s0
	v_lshl_add_u64 v[16:17], v[16:17], 1, s[8:9]
	s_waitcnt vmcnt(23)
	v_fmac_f32_e32 v46, v19, v109
	global_store_short v[16:17], v18, off sc1
	v_add_u32_e32 v16, v185, v32
	v_ashrrev_i32_e32 v17, 31, v16
	v_mul_f32_e32 v18, v48, v46
	v_cvt_pk_bf16_f32 v18, v18, s0
	v_lshl_add_u64 v[16:17], v[16:17], 1, s[8:9]
	global_store_short v[16:17], v18, off sc1
	v_or_b32_e32 v16, 0x60, v102
	v_ashrrev_i32_e32 v17, 31, v16
	v_fmac_f32_e32 v44, v20, v109
	s_waitcnt vmcnt(24)
	v_fmac_f32_e32 v43, v21, v109
	s_waitcnt vmcnt(23)
	v_fmac_f32_e32 v42, v22, v109
	s_waitcnt vmcnt(21)
	v_fmac_f32_e32 v41, v23, v109
	v_fmac_f32_e32 v40, v24, v109
	v_fmac_f32_e32 v39, v25, v109
	s_waitcnt vmcnt(20)
	v_fmac_f32_e32 v38, v26, v109
	s_waitcnt vmcnt(19)
	v_fmac_f32_e32 v37, v27, v109
	s_waitcnt vmcnt(18)
	v_fmac_f32_e32 v36, v28, v109
	s_waitcnt vmcnt(14)
	v_fmac_f32_e32 v35, v29, v109
	s_waitcnt vmcnt(13)
	v_fmac_f32_e32 v34, v30, v109
	s_waitcnt vmcnt(12)
	v_fmac_f32_e32 v33, v31, v109
	v_lshlrev_b64 v[20:21], 2, v[16:17]
	global_store_dword v[88:89], v45, off offset:256 sc1
	global_store_dword v[84:85], v47, off offset:256 sc1
	global_store_dword v[82:83], v46, off offset:256 sc1
	global_store_dword v[78:79], v44, off offset:256 sc1
	global_store_dword v[72:73], v43, off offset:256 sc1
	global_store_dword v[74:75], v42, off offset:256 sc1
	global_store_dword v[76:77], v41, off offset:256 sc1
	global_store_dword v[80:81], v40, off offset:256 sc1
	global_store_dword v[86:87], v39, off offset:256 sc1
	global_store_dword v[90:91], v38, off offset:256 sc1
	global_store_dword v[92:93], v37, off offset:256 sc1
	global_store_dword v[94:95], v36, off offset:256 sc1
	global_store_dword v[96:97], v35, off offset:256 sc1
	global_store_dword v[98:99], v34, off offset:256 sc1
	global_store_dword v[100:101], v33, off offset:256 sc1
	global_store_dword v[106:107], v116, off offset:256 sc1
	v_lshl_add_u64 v[22:23], s[60:61], 0, v[20:21]
	v_lshl_add_u64 v[20:21], s[62:63], 0, v[20:21]
	global_load_dword v29, v[106:107], off offset:384
	global_load_dword v102, v[22:23], off
	global_load_dword v17, v[20:21], off
	s_nop 0
	global_load_dword v20, v[104:105], off offset:384
	v_add_u32_e32 v18, v183, v32
	v_ashrrev_i32_e32 v19, 31, v18
	v_mul_f32_e32 v21, v48, v44
	v_cvt_pk_bf16_f32 v21, v21, s0
	v_lshl_add_u64 v[18:19], v[18:19], 1, s[8:9]
	global_store_short v[18:19], v21, off sc1
	v_add_u32_e32 v18, v181, v32
	v_ashrrev_i32_e32 v19, 31, v18
	v_mul_f32_e32 v21, v48, v43
	v_cvt_pk_bf16_f32 v21, v21, s0
	v_lshl_add_u64 v[18:19], v[18:19], 1, s[8:9]
	global_store_short v[18:19], v21, off sc1
	v_add_u32_e32 v18, v71, v32
	v_ashrrev_i32_e32 v19, 31, v18
	v_mul_f32_e32 v21, v48, v42
	v_cvt_pk_bf16_f32 v21, v21, s0
	v_lshl_add_u64 v[18:19], v[18:19], 1, s[8:9]
	global_store_short v[18:19], v21, off sc1
	v_add_u32_e32 v18, v182, v32
	v_ashrrev_i32_e32 v19, 31, v18
	v_mul_f32_e32 v21, v48, v41
	v_cvt_pk_bf16_f32 v21, v21, s0
	v_lshl_add_u64 v[18:19], v[18:19], 1, s[8:9]
	global_store_short v[18:19], v21, off sc1
	v_add_u32_e32 v18, v184, v32
	v_ashrrev_i32_e32 v19, 31, v18
	v_mul_f32_e32 v21, v48, v40
	v_cvt_pk_bf16_f32 v21, v21, s0
	v_lshl_add_u64 v[18:19], v[18:19], 1, s[8:9]
	global_store_short v[18:19], v21, off sc1
	v_add_u32_e32 v18, v187, v32
	v_ashrrev_i32_e32 v19, 31, v18
	v_mul_f32_e32 v21, v48, v39
	v_cvt_pk_bf16_f32 v21, v21, s0
	v_lshl_add_u64 v[18:19], v[18:19], 1, s[8:9]
	global_store_short v[18:19], v21, off sc1
	v_add_u32_e32 v18, v189, v32
	v_ashrrev_i32_e32 v19, 31, v18
	v_mul_f32_e32 v21, v48, v38
	v_cvt_pk_bf16_f32 v21, v21, s0
	v_lshl_add_u64 v[18:19], v[18:19], 1, s[8:9]
	global_store_short v[18:19], v21, off sc1
	v_add_u32_e32 v18, v191, v32
	v_ashrrev_i32_e32 v19, 31, v18
	v_mul_f32_e32 v21, v48, v37
	v_cvt_pk_bf16_f32 v21, v21, s0
	v_lshl_add_u64 v[18:19], v[18:19], 1, s[8:9]
	global_store_short v[18:19], v21, off sc1
	v_add_u32_e32 v18, v192, v32
	v_ashrrev_i32_e32 v19, 31, v18
	v_mul_f32_e32 v21, v48, v36
	v_cvt_pk_bf16_f32 v21, v21, s0
	v_lshl_add_u64 v[18:19], v[18:19], 1, s[8:9]
	global_load_dword v28, v[88:89], off offset:384
	global_load_dword v27, v[84:85], off offset:384
	global_load_dword v25, v[78:79], off offset:384
	global_load_dword v24, v[72:73], off offset:384
	global_load_dword v23, v[74:75], off offset:384
	v_mul_f32_e32 v30, v48, v33
	global_store_short v[18:19], v21, off sc1
	v_add_u32_e32 v18, v193, v32
	v_ashrrev_i32_e32 v19, 31, v18
	v_mul_f32_e32 v21, v48, v35
	v_cvt_pk_bf16_f32 v21, v21, s0
	v_lshl_add_u64 v[18:19], v[18:19], 1, s[8:9]
	global_store_short v[18:19], v21, off sc1
	v_add_u32_e32 v18, v194, v32
	v_ashrrev_i32_e32 v19, 31, v18
	v_mul_f32_e32 v21, v48, v34
	v_cvt_pk_bf16_f32 v21, v21, s0
	v_lshl_add_u64 v[18:19], v[18:19], 1, s[8:9]
	global_store_short v[18:19], v21, off sc1
	v_add_u32_e32 v18, v195, v32
	global_load_dword v21, v[80:81], off offset:384
	global_load_dword v22, v[76:77], off offset:384
	v_ashrrev_i32_e32 v19, 31, v18
	v_cvt_pk_bf16_f32 v30, v30, s0
	v_lshl_add_u64 v[18:19], v[18:19], 1, s[8:9]
	s_waitcnt vmcnt(19)
	v_add_f32_e32 v17, 1.0, v17
	s_waitcnt vmcnt(18)
	v_mul_f32_e32 v32, v20, v17
	global_load_dword v20, v[86:87], off offset:384
	global_load_dword v26, v[82:83], off offset:384
	v_fmac_f32_e32 v29, v0, v102
	global_store_short v[18:19], v30, off sc1
	v_add_u32_e32 v18, v190, v16
	v_ashrrev_i32_e32 v19, 31, v18
	v_mul_f32_e32 v0, v32, v29
	v_cvt_pk_bf16_f32 v0, v0, s0
	v_lshl_add_u64 v[18:19], v[18:19], 1, s[8:9]
	global_store_short v[18:19], v0, off sc1
	global_load_dword v19, v[90:91], off offset:384
	v_add_u32_e32 v30, v188, v16
	global_load_dword v18, v[92:93], off offset:384
	v_ashrrev_i32_e32 v31, 31, v30
	v_fmac_f32_e32 v108, v202, v202
	v_fmac_f32_e32 v108, v116, v116
	v_fmac_f32_e32 v108, v29, v29
	global_store_dword v[106:107], v29, off offset:384 sc1
	s_waitcnt vmcnt(16)
	v_fmac_f32_e32 v28, v1, v102
	v_mul_f32_e32 v0, v32, v28
	v_cvt_pk_bf16_f32 v17, v0, s0
	v_lshl_add_u64 v[0:1], v[30:31], 1, s[8:9]
	global_store_short v[0:1], v17, off sc1
	v_add_u32_e32 v0, v186, v16
	s_waitcnt vmcnt(16)
	v_fmac_f32_e32 v27, v2, v102
	global_load_dword v17, v[94:95], off offset:384
	v_ashrrev_i32_e32 v1, 31, v0
	v_mul_f32_e32 v2, v32, v27
	v_cvt_pk_bf16_f32 v2, v2, s0
	v_lshl_add_u64 v[0:1], v[0:1], 1, s[8:9]
	global_store_short v[0:1], v2, off sc1
	v_add_u32_e32 v0, v185, v16
	global_load_dword v2, v[96:97], off offset:384
	v_ashrrev_i32_e32 v1, 31, v0
	v_lshl_add_u64 v[0:1], v[0:1], 1, s[8:9]
	v_add_u32_e32 v30, v183, v16
	s_waitcnt vmcnt(18)
	v_fmac_f32_e32 v25, v4, v102
	v_ashrrev_i32_e32 v31, 31, v30
	v_lshl_add_u64 v[30:31], v[30:31], 1, s[8:9]
	s_waitcnt vmcnt(17)
	v_fmac_f32_e32 v24, v5, v102
	s_waitcnt vmcnt(16)
	v_fmac_f32_e32 v23, v6, v102
	s_waitcnt vmcnt(11)
	v_fmac_f32_e32 v22, v7, v102
	v_fmac_f32_e32 v21, v8, v102
	global_store_dword v[88:89], v28, off offset:384 sc1
	global_store_dword v[84:85], v27, off offset:384 sc1
	s_waitcnt vmcnt(12)
	v_fmac_f32_e32 v20, v9, v102
	s_waitcnt vmcnt(11)
	v_fmac_f32_e32 v26, v3, v102
	v_mul_f32_e32 v3, v32, v26
	v_cvt_pk_bf16_f32 v3, v3, s0
	global_store_short v[0:1], v3, off sc1
	global_load_dword v1, v[98:99], off offset:384
	v_mul_f32_e32 v0, v32, v25
	v_cvt_pk_bf16_f32 v0, v0, s0
	global_store_short v[30:31], v0, off sc1
	global_load_dword v0, v[100:101], off offset:384
	v_add_u32_e32 v30, v181, v16
	v_ashrrev_i32_e32 v31, 31, v30
	v_mul_f32_e32 v3, v32, v24
	v_cvt_pk_bf16_f32 v3, v3, s0
	v_lshl_add_u64 v[4:5], v[30:31], 1, s[8:9]
	global_store_short v[4:5], v3, off sc1
	v_add_u32_e32 v4, v71, v16
	v_ashrrev_i32_e32 v5, 31, v4
	v_mul_f32_e32 v3, v32, v23
	v_cvt_pk_bf16_f32 v3, v3, s0
	v_lshl_add_u64 v[4:5], v[4:5], 1, s[8:9]
	global_store_short v[4:5], v3, off sc1
	v_add_u32_e32 v4, v182, v16
	v_ashrrev_i32_e32 v5, 31, v4
	v_mul_f32_e32 v3, v32, v22
	v_cvt_pk_bf16_f32 v3, v3, s0
	v_lshl_add_u64 v[4:5], v[4:5], 1, s[8:9]
	global_store_short v[4:5], v3, off sc1
	v_add_u32_e32 v4, v184, v16
	v_ashrrev_i32_e32 v5, 31, v4
	v_mul_f32_e32 v3, v32, v21
	v_cvt_pk_bf16_f32 v3, v3, s0
	v_lshl_add_u64 v[4:5], v[4:5], 1, s[8:9]
	global_store_short v[4:5], v3, off sc1
	v_add_u32_e32 v4, v187, v16
	v_ashrrev_i32_e32 v5, 31, v4
	v_mul_f32_e32 v3, v32, v20
	v_cvt_pk_bf16_f32 v3, v3, s0
	v_lshl_add_u64 v[4:5], v[4:5], 1, s[8:9]
	global_store_short v[4:5], v3, off sc1
	v_add_u32_e32 v4, v189, v16
	s_waitcnt vmcnt(17)
	v_fmac_f32_e32 v19, v10, v102
	v_ashrrev_i32_e32 v5, 31, v4
	v_mul_f32_e32 v3, v32, v19
	v_cvt_pk_bf16_f32 v3, v3, s0
	v_lshl_add_u64 v[4:5], v[4:5], 1, s[8:9]
	global_store_short v[4:5], v3, off sc1
	v_add_u32_e32 v4, v191, v16
	s_waitcnt vmcnt(17)
	v_fmac_f32_e32 v18, v11, v102
	v_ashrrev_i32_e32 v5, 31, v4
	v_mul_f32_e32 v3, v32, v18
	v_cvt_pk_bf16_f32 v3, v3, s0
	v_lshl_add_u64 v[4:5], v[4:5], 1, s[8:9]
	global_store_short v[4:5], v3, off sc1
	v_add_u32_e32 v4, v192, v16
	v_ashrrev_i32_e32 v5, 31, v4
	v_lshl_add_u64 v[4:5], v[4:5], 1, s[8:9]
	v_add_u32_e32 v10, v195, v16
	v_ashrrev_i32_e32 v11, 31, v10
	v_lshl_add_u64 v[10:11], v[10:11], 1, s[8:9]
	s_waitcnt vmcnt(15)
	v_fmac_f32_e32 v17, v12, v102
	v_mul_f32_e32 v3, v32, v17
	v_cvt_pk_bf16_f32 v3, v3, s0
	global_store_short v[4:5], v3, off sc1
	v_add_u32_e32 v4, v193, v16
	v_ashrrev_i32_e32 v5, 31, v4
	v_lshl_add_u64 v[4:5], v[4:5], 1, s[8:9]
	s_waitcnt vmcnt(14)
	v_fmac_f32_e32 v2, v13, v102
	v_mul_f32_e32 v3, v32, v2
	v_cvt_pk_bf16_f32 v3, v3, s0
	global_store_short v[4:5], v3, off sc1
	v_add_u32_e32 v4, v194, v16
	v_ashrrev_i32_e32 v5, 31, v4
	v_lshl_add_u64 v[4:5], v[4:5], 1, s[8:9]
	v_xor_b32_e32 v13, 16, v166
	v_ashrrev_i32_e32 v71, 31, v70
	global_store_dword v[82:83], v26, off offset:384 sc1
	global_store_dword v[78:79], v25, off offset:384 sc1
	global_store_dword v[72:73], v24, off offset:384 sc1
	global_store_dword v[74:75], v23, off offset:384 sc1
	global_store_dword v[76:77], v22, off offset:384 sc1
	global_store_dword v[80:81], v21, off offset:384 sc1
	global_store_dword v[86:87], v20, off offset:384 sc1
	global_store_dword v[90:91], v19, off offset:384 sc1
	global_store_dword v[92:93], v18, off offset:384 sc1
	s_waitcnt vmcnt(20)
	v_fmac_f32_e32 v1, v14, v102
	v_mul_f32_e32 v3, v32, v1
	v_cvt_pk_bf16_f32 v3, v3, s0
	global_store_short v[4:5], v3, off sc1
	v_and_b32_e32 v4, 64, v166
	v_xor_b32_e32 v3, 1, v166
	v_add_u32_e32 v7, 64, v4
	v_cmp_lt_i32_e32 vcc, v3, v7
	v_xor_b32_e32 v4, 2, v166
	s_waitcnt vmcnt(19)
	v_fmac_f32_e32 v0, v15, v102
	v_cndmask_b32_e32 v3, v166, v3, vcc
	v_lshlrev_b32_e32 v3, 2, v3
	ds_bpermute_b32 v5, v3, v108
	v_cmp_lt_i32_e32 vcc, v4, v7
	v_mul_f32_e32 v12, v32, v0
	v_cvt_pk_bf16_f32 v12, v12, s0
	v_cndmask_b32_e32 v4, v166, v4, vcc
	v_lshlrev_b32_e32 v4, 2, v4
	s_waitcnt lgkmcnt(0)
	v_add_f32_e32 v6, v108, v5
	ds_bpermute_b32 v8, v4, v6
	v_xor_b32_e32 v5, 4, v166
	v_cmp_lt_i32_e32 vcc, v5, v7
	global_store_dword v[94:95], v17, off offset:384 sc1
	global_store_dword v[96:97], v2, off offset:384 sc1
	v_cndmask_b32_e32 v5, v166, v5, vcc
	v_lshlrev_b32_e32 v5, 2, v5
	s_waitcnt lgkmcnt(0)
	v_add_f32_e32 v8, v6, v8
	ds_bpermute_b32 v9, v5, v8
	v_xor_b32_e32 v6, 8, v166
	v_cmp_lt_i32_e32 vcc, v6, v7
	global_store_dword v[98:99], v1, off offset:384 sc1
	global_store_dword v[100:101], v0, off offset:384 sc1
	v_cndmask_b32_e32 v6, v166, v6, vcc
	v_lshlrev_b32_e32 v6, 2, v6
	s_waitcnt lgkmcnt(0)
	v_add_f32_e32 v8, v8, v9
	ds_bpermute_b32 v9, v6, v8
	v_cmp_lt_i32_e32 vcc, v13, v7
	global_store_short v[10:11], v12, off sc1
	s_waitcnt lgkmcnt(0)
	v_add_f32_e32 v8, v8, v9
	v_cndmask_b32_e32 v7, v166, v13, vcc
	v_lshlrev_b32_e32 v7, 2, v7
	ds_bpermute_b32 v9, v7, v8
	s_and_saveexec_b64 s[60:61], s[0:1]
	s_cbranch_execz .LBB0_709
	s_waitcnt lgkmcnt(0)
	v_add_f32_e32 v10, v8, v9
	v_lshl_add_u64 v[8:9], v[70:71], 2, s[58:59]
	global_store_dword v[8:9], v10, off sc1
.LBB0_709:
	s_or_b64 exec, exec, s[60:61]
	v_mul_f32_e32 v8, v63, v63
	v_fmac_f32_e32 v8, v180, v180
	v_fmac_f32_e32 v8, v45, v45
	v_fmac_f32_e32 v8, v28, v28
	s_waitcnt lgkmcnt(0)
	ds_bpermute_b32 v9, v3, v8
	s_waitcnt lgkmcnt(0)
	v_add_f32_e32 v8, v8, v9
	ds_bpermute_b32 v9, v4, v8
	s_waitcnt lgkmcnt(0)
	v_add_f32_e32 v8, v8, v9
	ds_bpermute_b32 v9, v5, v8
	s_waitcnt lgkmcnt(0)
	v_add_f32_e32 v8, v8, v9
	ds_bpermute_b32 v9, v6, v8
	s_waitcnt lgkmcnt(0)
	v_add_f32_e32 v8, v8, v9
	ds_bpermute_b32 v9, v7, v8
	s_and_saveexec_b64 s[60:61], s[0:1]
	s_cbranch_execz .LBB0_711
	s_waitcnt lgkmcnt(0)
	v_add_f32_e32 v10, v8, v9
	v_lshl_add_u64 v[8:9], v[70:71], 2, s[58:59]
	global_store_dword v[8:9], v10, off offset:4 sc1
.LBB0_711:
	s_or_b64 exec, exec, s[60:61]
	v_mul_f32_e32 v8, v62, v62
	v_fmac_f32_e32 v8, v179, v179
	v_fmac_f32_e32 v8, v47, v47
	v_fmac_f32_e32 v8, v27, v27
	s_waitcnt lgkmcnt(0)
	ds_bpermute_b32 v9, v3, v8
	s_waitcnt lgkmcnt(0)
	v_add_f32_e32 v8, v8, v9
	ds_bpermute_b32 v9, v4, v8
	s_waitcnt lgkmcnt(0)
	v_add_f32_e32 v8, v8, v9
	ds_bpermute_b32 v9, v5, v8
	s_waitcnt lgkmcnt(0)
	v_add_f32_e32 v8, v8, v9
	ds_bpermute_b32 v9, v6, v8
	s_waitcnt lgkmcnt(0)
	v_add_f32_e32 v8, v8, v9
	ds_bpermute_b32 v9, v7, v8
	s_and_saveexec_b64 s[60:61], s[0:1]
	s_cbranch_execz .LBB0_713
	s_waitcnt lgkmcnt(0)
	v_add_f32_e32 v10, v8, v9
	v_lshl_add_u64 v[8:9], v[70:71], 2, s[58:59]
	global_store_dword v[8:9], v10, off offset:8 sc1
.LBB0_713:
	s_or_b64 exec, exec, s[60:61]
	v_mul_f32_e32 v8, v61, v61
	v_fmac_f32_e32 v8, v178, v178
	v_fmac_f32_e32 v8, v46, v46
	v_fmac_f32_e32 v8, v26, v26
	s_waitcnt lgkmcnt(0)
	ds_bpermute_b32 v9, v3, v8
	s_waitcnt lgkmcnt(0)
	v_add_f32_e32 v8, v8, v9
	ds_bpermute_b32 v9, v4, v8
	s_waitcnt lgkmcnt(0)
	v_add_f32_e32 v8, v8, v9
	ds_bpermute_b32 v9, v5, v8
	s_waitcnt lgkmcnt(0)
	v_add_f32_e32 v8, v8, v9
	ds_bpermute_b32 v9, v6, v8
	s_waitcnt lgkmcnt(0)
	v_add_f32_e32 v8, v8, v9
	ds_bpermute_b32 v9, v7, v8
	s_and_saveexec_b64 s[60:61], s[0:1]
	s_cbranch_execz .LBB0_715
	s_waitcnt lgkmcnt(0)
	v_add_f32_e32 v10, v8, v9
	v_lshl_add_u64 v[8:9], v[70:71], 2, s[58:59]
	global_store_dword v[8:9], v10, off offset:12 sc1
.LBB0_715:
	s_or_b64 exec, exec, s[60:61]
	v_mul_f32_e32 v8, v60, v60
	v_fmac_f32_e32 v8, v177, v177
	v_fmac_f32_e32 v8, v44, v44
	v_fmac_f32_e32 v8, v25, v25
	s_waitcnt lgkmcnt(0)
	ds_bpermute_b32 v9, v3, v8
	s_waitcnt lgkmcnt(0)
	v_add_f32_e32 v8, v8, v9
	ds_bpermute_b32 v9, v4, v8
	s_waitcnt lgkmcnt(0)
	v_add_f32_e32 v8, v8, v9
	ds_bpermute_b32 v9, v5, v8
	s_waitcnt lgkmcnt(0)
	v_add_f32_e32 v8, v8, v9
	ds_bpermute_b32 v9, v6, v8
	s_waitcnt lgkmcnt(0)
	v_add_f32_e32 v8, v8, v9
	ds_bpermute_b32 v9, v7, v8
	s_and_saveexec_b64 s[60:61], s[0:1]
	s_cbranch_execz .LBB0_717
	s_waitcnt lgkmcnt(0)
	v_add_f32_e32 v10, v8, v9
	v_lshl_add_u64 v[8:9], v[70:71], 2, s[58:59]
	global_store_dword v[8:9], v10, off offset:32 sc1
.LBB0_717:
	s_or_b64 exec, exec, s[60:61]
	v_mul_f32_e32 v8, v59, v59
	v_fmac_f32_e32 v8, v176, v176
	v_fmac_f32_e32 v8, v43, v43
	v_fmac_f32_e32 v8, v24, v24
	s_waitcnt lgkmcnt(0)
	ds_bpermute_b32 v9, v3, v8
	s_waitcnt lgkmcnt(0)
	v_add_f32_e32 v8, v8, v9
	ds_bpermute_b32 v9, v4, v8
	s_waitcnt lgkmcnt(0)
	v_add_f32_e32 v8, v8, v9
	ds_bpermute_b32 v9, v5, v8
	s_waitcnt lgkmcnt(0)
	v_add_f32_e32 v8, v8, v9
	ds_bpermute_b32 v9, v6, v8
	s_waitcnt lgkmcnt(0)
	v_add_f32_e32 v8, v8, v9
	ds_bpermute_b32 v9, v7, v8
	s_and_saveexec_b64 s[60:61], s[0:1]
	s_cbranch_execz .LBB0_719
	s_waitcnt lgkmcnt(0)
	v_add_f32_e32 v10, v8, v9
	v_lshl_add_u64 v[8:9], v[70:71], 2, s[58:59]
	global_store_dword v[8:9], v10, off offset:36 sc1
.LBB0_719:
	s_or_b64 exec, exec, s[60:61]
	v_mul_f32_e32 v8, v58, v58
	v_fmac_f32_e32 v8, v175, v175
	v_fmac_f32_e32 v8, v42, v42
	v_fmac_f32_e32 v8, v23, v23
	s_waitcnt lgkmcnt(0)
	ds_bpermute_b32 v9, v3, v8
	s_waitcnt lgkmcnt(0)
	v_add_f32_e32 v8, v8, v9
	ds_bpermute_b32 v9, v4, v8
	s_waitcnt lgkmcnt(0)
	v_add_f32_e32 v8, v8, v9
	ds_bpermute_b32 v9, v5, v8
	s_waitcnt lgkmcnt(0)
	v_add_f32_e32 v8, v8, v9
	ds_bpermute_b32 v9, v6, v8
	s_waitcnt lgkmcnt(0)
	v_add_f32_e32 v8, v8, v9
	ds_bpermute_b32 v9, v7, v8
	s_and_saveexec_b64 s[60:61], s[0:1]
	s_cbranch_execz .LBB0_721
	s_waitcnt lgkmcnt(0)
	v_add_f32_e32 v10, v8, v9
	v_lshl_add_u64 v[8:9], v[70:71], 2, s[58:59]
	global_store_dword v[8:9], v10, off offset:40 sc1
.LBB0_721:
	s_or_b64 exec, exec, s[60:61]
	v_mul_f32_e32 v8, v57, v57
	v_fmac_f32_e32 v8, v174, v174
	v_fmac_f32_e32 v8, v41, v41
	v_fmac_f32_e32 v8, v22, v22
	s_waitcnt lgkmcnt(0)
	ds_bpermute_b32 v9, v3, v8
	s_waitcnt lgkmcnt(0)
	v_add_f32_e32 v8, v8, v9
	ds_bpermute_b32 v9, v4, v8
	s_waitcnt lgkmcnt(0)
	v_add_f32_e32 v8, v8, v9
	ds_bpermute_b32 v9, v5, v8
	s_waitcnt lgkmcnt(0)
	v_add_f32_e32 v8, v8, v9
	ds_bpermute_b32 v9, v6, v8
	s_waitcnt lgkmcnt(0)
	v_add_f32_e32 v8, v8, v9
	ds_bpermute_b32 v9, v7, v8
	s_and_saveexec_b64 s[60:61], s[0:1]
	s_cbranch_execz .LBB0_723
	s_waitcnt lgkmcnt(0)
	v_add_f32_e32 v10, v8, v9
	v_lshl_add_u64 v[8:9], v[70:71], 2, s[58:59]
	global_store_dword v[8:9], v10, off offset:44 sc1
.LBB0_723:
	s_or_b64 exec, exec, s[60:61]
	v_mul_f32_e32 v8, v56, v56
	v_fmac_f32_e32 v8, v173, v173
	v_fmac_f32_e32 v8, v40, v40
	v_fmac_f32_e32 v8, v21, v21
	s_waitcnt lgkmcnt(0)
	ds_bpermute_b32 v9, v3, v8
	s_waitcnt lgkmcnt(0)
	v_add_f32_e32 v8, v8, v9
	ds_bpermute_b32 v9, v4, v8
	s_waitcnt lgkmcnt(0)
	v_add_f32_e32 v8, v8, v9
	ds_bpermute_b32 v9, v5, v8
	s_waitcnt lgkmcnt(0)
	v_add_f32_e32 v8, v8, v9
	ds_bpermute_b32 v9, v6, v8
	s_waitcnt lgkmcnt(0)
	v_add_f32_e32 v8, v8, v9
	ds_bpermute_b32 v9, v7, v8
	s_and_saveexec_b64 s[60:61], s[0:1]
	s_cbranch_execz .LBB0_725
	s_waitcnt lgkmcnt(0)
	v_add_f32_e32 v10, v8, v9
	v_lshl_add_u64 v[8:9], v[70:71], 2, s[58:59]
	global_store_dword v[8:9], v10, off offset:64 sc1
.LBB0_725:
	s_or_b64 exec, exec, s[60:61]
	v_mul_f32_e32 v8, v55, v55
	v_fmac_f32_e32 v8, v172, v172
	v_fmac_f32_e32 v8, v39, v39
	v_fmac_f32_e32 v8, v20, v20
	s_waitcnt lgkmcnt(0)
	ds_bpermute_b32 v9, v3, v8
	s_waitcnt lgkmcnt(0)
	v_add_f32_e32 v8, v8, v9
	ds_bpermute_b32 v9, v4, v8
	s_waitcnt lgkmcnt(0)
	v_add_f32_e32 v8, v8, v9
	ds_bpermute_b32 v9, v5, v8
	s_waitcnt lgkmcnt(0)
	v_add_f32_e32 v8, v8, v9
	ds_bpermute_b32 v9, v6, v8
	s_waitcnt lgkmcnt(0)
	v_add_f32_e32 v8, v8, v9
	ds_bpermute_b32 v9, v7, v8
	s_and_saveexec_b64 s[60:61], s[0:1]
	s_cbranch_execz .LBB0_727
	s_waitcnt lgkmcnt(0)
	v_add_f32_e32 v10, v8, v9
	v_lshl_add_u64 v[8:9], v[70:71], 2, s[58:59]
	global_store_dword v[8:9], v10, off offset:68 sc1
.LBB0_727:
	s_or_b64 exec, exec, s[60:61]
	v_mul_f32_e32 v8, v54, v54
	v_fmac_f32_e32 v8, v170, v170
	v_fmac_f32_e32 v8, v38, v38
	v_fmac_f32_e32 v8, v19, v19
	s_waitcnt lgkmcnt(0)
	ds_bpermute_b32 v9, v3, v8
	s_waitcnt lgkmcnt(0)
	v_add_f32_e32 v8, v8, v9
	ds_bpermute_b32 v9, v4, v8
	s_waitcnt lgkmcnt(0)
	v_add_f32_e32 v8, v8, v9
	ds_bpermute_b32 v9, v5, v8
	s_waitcnt lgkmcnt(0)
	v_add_f32_e32 v8, v8, v9
	ds_bpermute_b32 v9, v6, v8
	s_waitcnt lgkmcnt(0)
	v_add_f32_e32 v8, v8, v9
	ds_bpermute_b32 v9, v7, v8
	s_and_saveexec_b64 s[60:61], s[0:1]
	s_cbranch_execz .LBB0_729
	s_waitcnt lgkmcnt(0)
	v_add_f32_e32 v10, v8, v9
	v_lshl_add_u64 v[8:9], v[70:71], 2, s[58:59]
	global_store_dword v[8:9], v10, off offset:72 sc1
.LBB0_729:
	s_or_b64 exec, exec, s[60:61]
	v_mul_f32_e32 v8, v53, v53
	v_fmac_f32_e32 v8, v171, v171
	v_fmac_f32_e32 v8, v37, v37
	v_fmac_f32_e32 v8, v18, v18
	s_waitcnt lgkmcnt(0)
	ds_bpermute_b32 v9, v3, v8
	s_waitcnt lgkmcnt(0)
	v_add_f32_e32 v8, v8, v9
	ds_bpermute_b32 v9, v4, v8
	s_waitcnt lgkmcnt(0)
	v_add_f32_e32 v8, v8, v9
	ds_bpermute_b32 v9, v5, v8
	s_waitcnt lgkmcnt(0)
	v_add_f32_e32 v8, v8, v9
	ds_bpermute_b32 v9, v6, v8
	s_waitcnt lgkmcnt(0)
	v_add_f32_e32 v8, v8, v9
	ds_bpermute_b32 v9, v7, v8
	s_and_saveexec_b64 s[60:61], s[0:1]
	s_cbranch_execz .LBB0_731
	s_waitcnt lgkmcnt(0)
	v_add_f32_e32 v10, v8, v9
	v_lshl_add_u64 v[8:9], v[70:71], 2, s[58:59]
	global_store_dword v[8:9], v10, off offset:76 sc1
.LBB0_731:
	s_or_b64 exec, exec, s[60:61]
	v_mul_f32_e32 v8, v52, v52
	v_fmac_f32_e32 v8, v169, v169
	v_fmac_f32_e32 v8, v36, v36
	v_fmac_f32_e32 v8, v17, v17
	s_waitcnt lgkmcnt(0)
	ds_bpermute_b32 v9, v3, v8
	s_waitcnt lgkmcnt(0)
	v_add_f32_e32 v8, v8, v9
	ds_bpermute_b32 v9, v4, v8
	s_waitcnt lgkmcnt(0)
	v_add_f32_e32 v8, v8, v9
	ds_bpermute_b32 v9, v5, v8
	s_waitcnt lgkmcnt(0)
	v_add_f32_e32 v8, v8, v9
	ds_bpermute_b32 v9, v6, v8
	s_waitcnt lgkmcnt(0)
	v_add_f32_e32 v8, v8, v9
	ds_bpermute_b32 v9, v7, v8
	s_and_saveexec_b64 s[60:61], s[0:1]
	s_cbranch_execz .LBB0_733
	s_waitcnt lgkmcnt(0)
	v_add_f32_e32 v10, v8, v9
	v_lshl_add_u64 v[8:9], v[70:71], 2, s[58:59]
	global_store_dword v[8:9], v10, off offset:96 sc1
.LBB0_733:
	s_or_b64 exec, exec, s[60:61]
	v_mul_f32_e32 v8, v51, v51
	v_fmac_f32_e32 v8, v168, v168
	v_fmac_f32_e32 v8, v35, v35
	v_fmac_f32_e32 v8, v2, v2
	ds_bpermute_b32 v2, v3, v8
	s_waitcnt lgkmcnt(0)
	v_add_f32_e32 v2, v8, v2
	ds_bpermute_b32 v8, v4, v2
	s_waitcnt lgkmcnt(0)
	v_add_f32_e32 v2, v2, v8
	ds_bpermute_b32 v8, v5, v2
	s_waitcnt lgkmcnt(0)
	v_add_f32_e32 v2, v2, v8
	ds_bpermute_b32 v8, v6, v2
	s_waitcnt lgkmcnt(0)
	v_add_f32_e32 v2, v2, v8
	ds_bpermute_b32 v8, v7, v2
	s_and_saveexec_b64 s[60:61], s[0:1]
	s_cbranch_execz .LBB0_735
	s_waitcnt lgkmcnt(0)
	v_add_f32_e32 v2, v2, v8
	v_lshl_add_u64 v[8:9], v[70:71], 2, s[58:59]
	global_store_dword v[8:9], v2, off offset:100 sc1
.LBB0_735:
	s_or_b64 exec, exec, s[60:61]
	v_mul_f32_e32 v2, v50, v50
	v_fmac_f32_e32 v2, v167, v167
	v_fmac_f32_e32 v2, v34, v34
	v_fmac_f32_e32 v2, v1, v1
	ds_bpermute_b32 v1, v3, v2
	s_waitcnt lgkmcnt(0)
	v_add_f32_e32 v1, v2, v1
	ds_bpermute_b32 v2, v4, v1
	s_waitcnt lgkmcnt(0)
	v_add_f32_e32 v1, v1, v2
	ds_bpermute_b32 v2, v5, v1
	s_waitcnt lgkmcnt(0)
	v_add_f32_e32 v1, v1, v2
	ds_bpermute_b32 v2, v6, v1
	s_waitcnt lgkmcnt(0)
	v_add_f32_e32 v1, v1, v2
	ds_bpermute_b32 v2, v7, v1
	s_and_saveexec_b64 s[60:61], s[0:1]
	s_cbranch_execz .LBB0_737
	s_waitcnt lgkmcnt(0)
	v_add_f32_e32 v1, v1, v2
	v_lshl_add_u64 v[8:9], v[70:71], 2, s[58:59]
	global_store_dword v[8:9], v1, off offset:104 sc1
.LBB0_737:
	s_or_b64 exec, exec, s[60:61]
	v_mul_f32_e32 v1, v49, v49
	v_fmac_f32_e32 v1, v103, v103
	v_fmac_f32_e32 v1, v33, v33
	v_fmac_f32_e32 v1, v0, v0
	ds_bpermute_b32 v0, v3, v1
	s_waitcnt lgkmcnt(0)
	v_add_f32_e32 v0, v1, v0
	ds_bpermute_b32 v1, v4, v0
	s_waitcnt lgkmcnt(0)
	v_add_f32_e32 v0, v0, v1
	ds_bpermute_b32 v1, v5, v0
	s_waitcnt lgkmcnt(0)
	v_add_f32_e32 v0, v0, v1
	ds_bpermute_b32 v1, v6, v0
	s_waitcnt lgkmcnt(0)
	v_add_f32_e32 v0, v0, v1
	ds_bpermute_b32 v1, v7, v0
	s_and_saveexec_b64 s[60:61], s[0:1]
	s_cbranch_execz .LBB0_702
	s_waitcnt lgkmcnt(0)
	v_add_f32_e32 v2, v0, v1
	v_lshl_add_u64 v[0:1], v[70:71], 2, s[58:59]
	global_store_dword v[0:1], v2, off offset:108 sc1
	s_branch .LBB0_702
.LBB0_739:
	s_cmp_gt_i32 s17, 7
	s_cselect_b64 s[6:7], -1, 0
	s_and_b64 s[0:1], s[4:5], s[6:7]
	s_andn2_b64 vcc, exec, s[0:1]
	s_cbranch_vccnz .LBB0_751
	s_waitcnt vmcnt(0)
	v_or_b32_e32 v0, v201, v200
	s_movk_i32 s0, 0x3ff
	v_and_or_b32 v0, v0, s0, v199
	v_cmp_eq_u32_e32 vcc, 0, v0
	s_waitcnt lgkmcnt(0)
	s_barrier
	s_and_saveexec_b64 s[0:1], vcc
	s_cbranch_execz .LBB0_750
	s_add_u32 s4, s14, 0x5be8c00
	s_addc_u32 s5, s15, 0
	s_lshl_b32 s3, s2, 1
	v_mov_b32_e32 v0, s3
	v_mov_b32_e32 v1, 0x9307
	global_store_short v0, v1, s[4:5] sc1
	s_cmp_lg_u32 s2, 0
	s_cbranch_scc1 .Lgbar_wait_6
	s_lshr_b32 s3, s33, 3
	s_bfm_b64 s[8:9], s3, 0
	s_cmpk_gt_u32 s33, 0x1ff
	s_cselect_b64 s[8:9], -1, s[8:9]
	s_mov_b64 exec, -1
	v_mbcnt_lo_u32_b32 v229, -1, 0
	v_mbcnt_hi_u32_b32 v229, -1, v229
	v_lshlrev_b32_e32 v229, 4, v229
	s_mov_b32 s10, 0x93079307
	s_mov_b64 exec, s[8:9]

.LBB0_751:
	s_cmp_lt_i32 s16, 8
	s_cselect_b64 s[0:1], -1, 0
	s_and_b64 s[4:5], s[0:1], s[6:7]
	s_andn2_b64 vcc, exec, s[4:5]
	s_cbranch_vccnz .LBB0_759
	s_ashr_i32 s3, s2, 31
	s_and_b32 s3, s3, s33
	s_add_i32 s3, s3, s2
	s_cmpk_gt_i32 s3, 0x15ff
	s_cbranch_scc1 .LBB0_759
	v_lshrrev_b32_e32 v0, 3, v199
	s_waitcnt lgkmcnt(0)
	v_lshrrev_b32_e32 v1, 5, v199
	v_bfe_u32 v4, v199, 1, 3
	v_lshlrev_b32_e32 v5, 4, v199
	v_bfe_u32 v2, v199, 5, 1
	v_xor_b32_e32 v6, v5, v199
	v_lshlrev_b32_e32 v7, 11, v0
	s_movk_i32 s4, 0x70
	v_bitop3_b32 v1, v1, v4, 1 bitop3:0x6c
	v_and_or_b32 v76, v6, s4, v7
	v_lshlrev_b32_e32 v7, 4, v1
	v_bitop3_b32 v1, v2, v4, 2 bitop3:0x36
	v_lshrrev_b32_e32 v3, 1, v199
	v_lshlrev_b32_e32 v9, 4, v1
	v_bitop3_b32 v1, v2, v4, 4 bitop3:0x36
	v_mov_b32_e32 v77, 0
	v_and_b32_e32 v3, 0x1e0, v3
	v_lshlrev_b32_e32 v10, 4, v1
	v_bitop3_b32 v1, v2, v4, 6 bitop3:0x36
	v_lshlrev_b32_e32 v2, 4, v1
	v_and_or_b32 v93, v0, 4, v3
	v_lshl_add_u64 v[0:1], s[14:15], 0, v[76:77]
	s_mov_b64 s[6:7], 0x679f000
	v_lshl_add_u64 v[78:79], v[0:1], 0, s[6:7]
	s_mov_b64 s[6:7], 0x19a0000
	v_lshl_add_u64 v[80:81], v[0:1], 0, s[6:7]
	s_add_u32 s6, s14, 0x5cce000
	s_addc_u32 s7, s15, 0
	v_and_b32_e32 v92, 31, v199
	s_add_u32 s10, s14, 0x5c0c000
	v_or_b32_e32 v6, v3, v92
	s_addc_u32 s11, s15, 0
	v_lshl_add_u32 v6, v6, 7, 0
	v_lshl_add_u32 v8, v92, 7, 0
	s_add_u32 s8, s14, 0x879f000
	v_add_u32_e32 v94, 0, v5
	s_mov_b32 s5, 0
	s_addc_u32 s9, s15, 0
	v_add_u32_e32 v95, 0x4000, v94
	s_mov_b64 s[18:19], 0x10000
	v_add_u32_e32 v96, 0x1000, v94
	v_add_u32_e32 v97, 0x5000, v94
	s_mov_b64 s[20:21], 0x20000
	v_add_u32_e32 v98, 0x2000, v94
	v_add_u32_e32 v99, 0x6000, v94
	s_mov_b64 s[22:23], 0x30000
	v_add_u32_e32 v100, 0x3000, v94
	v_add_u32_e32 v101, 0x7000, v94
	s_mov_b64 s[24:25], 0x679f080
	s_mov_b64 s[26:27], 0x19a0080
	v_add_u32_e32 v102, 0x8000, v94
	v_add_u32_e32 v103, 0xc000, v94
	s_mov_b64 s[28:29], 0x67af080
	v_add_u32_e32 v104, 0x9000, v94
	s_mov_b64 s[30:31], 0x19b0080
	v_add_u32_e32 v105, 0xd000, v94
	s_mov_b64 s[34:35], 0x67bf080
	v_add_u32_e32 v106, 0xa000, v94
	s_mov_b64 s[36:37], 0x19c0080
	v_add_u32_e32 v107, 0xe000, v94
	s_mov_b64 s[38:39], 0x67cf080
	v_add_u32_e32 v108, 0xb000, v94
	s_mov_b64 s[40:41], 0x19d0080
	v_add_u32_e32 v109, 0xf000, v94
	v_add_u32_e32 v110, v6, v7
	v_add_u32_e32 v111, v8, v7
	v_add_u32_e32 v112, v6, v9
	v_add_u32_e32 v113, v8, v9
	v_add_u32_e32 v114, v6, v10
	v_add_u32_e32 v115, v8, v10
	v_add_u32_e32 v116, v6, v2
	v_add_u32_e32 v117, v8, v2
	s_mov_b64 s[42:43], 0x679f100
	s_mov_b64 s[44:45], 0x19a0100
	s_mov_b64 s[46:47], 0x67af100
	s_mov_b64 s[48:49], 0x19b0100
	s_mov_b64 s[50:51], 0x67bf100
	s_mov_b64 s[52:53], 0x19c0100
	s_mov_b64 s[54:55], 0x67cf100
	s_mov_b64 s[56:57], 0x19d0100
	s_movk_i32 s68, 0x1600
	s_mov_b32 s69, 0x10000
	s_mov_b32 s70, 0x20000
	s_mov_b32 s71, 0x30000
	s_mov_b32 s72, 0x40000
	s_mov_b32 s73, 0x50000
	s_mov_b32 s74, 0x60000
	s_mov_b32 s75, 0x70000
	v_mov_b32_e32 v118, 0x358637bd
	s_mov_b32 s39, 0
	s_branch .LBB0_755
.LBB0_754:
	v_add_u32_e32 v82, s60, v93
	v_ashrrev_i32_e32 v83, 31, v82
	v_lshl_add_u64 v[64:65], v[82:83], 2, s[6:7]
	v_add_co_u32_e32 v66, vcc, s69, v64
	v_or_b32_e32 v84, 8, v82
	s_nop 0
	v_addc_co_u32_e32 v67, vcc, 0, v65, vcc
	global_load_dwordx4 v[86:89], v[64:65], off
	global_load_dwordx4 v[122:125], v[66:67], off
	v_add_co_u32_e32 v66, vcc, s70, v64
	v_ashrrev_i32_e32 v85, 31, v84
	s_nop 0
	v_addc_co_u32_e32 v67, vcc, 0, v65, vcc
	v_add_co_u32_e32 v68, vcc, s71, v64
	v_lshl_add_u64 v[90:91], v[84:85], 2, s[6:7]
	s_nop 0
	v_addc_co_u32_e32 v69, vcc, 0, v65, vcc
	global_load_dwordx4 v[126:129], v[66:67], off
	global_load_dwordx4 v[130:133], v[68:69], off
	v_add_co_u32_e32 v66, vcc, s72, v64
	s_add_i32 s59, s60, 0xffffe000
	s_nop 0
	v_addc_co_u32_e32 v67, vcc, 0, v65, vcc
	v_add_co_u32_e32 v68, vcc, s73, v64
	s_lshr_b32 s59, s59, 12
	s_nop 0
	v_addc_co_u32_e32 v69, vcc, 0, v65, vcc
	global_load_dwordx4 v[134:137], v[66:67], off
	global_load_dwordx4 v[138:141], v[68:69], off
	v_add_co_u32_e32 v66, vcc, s74, v64
	s_mulk_i32 s59, 0x1600
	s_nop 0
	v_addc_co_u32_e32 v67, vcc, 0, v65, vcc
	v_add_co_u32_e32 v68, vcc, s75, v64
	s_addk_i32 s59, 0x1600
	s_nop 0
	v_addc_co_u32_e32 v69, vcc, 0, v65, vcc
	global_load_dwordx4 v[64:67], v[66:67], off
	s_nop 0
	global_load_dwordx4 v[68:71], v[68:69], off
	v_add_co_u32_e32 v72, vcc, s69, v90
	s_cmp_gt_i32 s4, 63
	s_nop 0
	v_addc_co_u32_e32 v73, vcc, 0, v91, vcc
	v_add_co_u32_e32 v142, vcc, s70, v90
	global_load_dword v85, v[90:91], off
	s_nop 0
	global_load_dwordx4 v[72:75], v[72:73], off
	v_addc_co_u32_e32 v143, vcc, 0, v91, vcc
	s_cselect_b32 s4, s59, 0
	s_lshl_b64 s[60:61], s[4:5], 2
	s_add_u32 s60, s10, s60
	s_addc_u32 s61, s11, s61
	v_or_b32_e32 v120, 1, v82
	v_or_b32_e32 v119, 2, v82
	v_or_b32_e32 v83, 3, v82
	s_add_i32 s3, s3, s33
	s_cmpk_gt_i32 s3, 0x15ff
	s_waitcnt vmcnt(0)
	v_add_f32_e32 v86, v86, v122
	v_add_f32_e32 v88, v88, v124
	v_add_f32_e32 v89, v89, v125
	v_add_f32_e32 v87, v87, v123
	v_add_f32_e32 v121, v126, v130
	v_add_f32_e32 v124, v129, v133
	v_add_f32_e32 v122, v127, v131
	v_add_f32_e32 v86, v86, v121
	v_add_f32_e32 v121, v89, v124
	v_add_f32_e32 v87, v87, v122
	v_add_f32_e32 v123, v128, v132
	v_add_f32_e32 v88, v88, v123
	v_add_f32_e32 v89, v134, v138
	v_add_f32_e32 v122, v135, v139
	v_add_f32_e32 v123, v136, v140
	v_add_f32_e32 v198, v137, v141
	v_add_f32_e32 v64, v64, v68
	v_add_f32_e32 v65, v65, v69
	v_add_f32_e32 v64, v89, v64
	v_add_f32_e32 v66, v66, v70
	v_add_f32_e32 v65, v122, v65
	v_add_f32_e32 v70, v86, v64
	v_add_co_u32_e32 v64, vcc, s71, v90
	v_add_f32_e32 v209, v87, v65
	s_nop 0
	v_addc_co_u32_e32 v65, vcc, 0, v91, vcc
	v_add_f32_e32 v66, v123, v66
	global_load_dwordx4 v[122:125], v[142:143], off
	global_load_dwordx4 v[126:129], v[64:65], off
	v_add_co_u32_e32 v64, vcc, s72, v90
	v_add_f32_e32 v213, v88, v66
	s_nop 0
	v_addc_co_u32_e32 v65, vcc, 0, v91, vcc
	v_add_co_u32_e32 v68, vcc, s73, v90
	v_add_f32_e32 v66, v67, v71
	s_nop 0
	v_addc_co_u32_e32 v69, vcc, 0, v91, vcc
	global_load_dwordx4 v[130:133], v[64:65], off
	global_load_dwordx4 v[134:137], v[68:69], off
	v_add_co_u32_e32 v64, vcc, s74, v90
	v_add_f32_e32 v66, v198, v66
	s_nop 0
	v_addc_co_u32_e32 v65, vcc, 0, v91, vcc
	v_add_co_u32_e32 v68, vcc, s75, v90
	v_add_f32_e32 v71, v121, v66
	s_nop 0
	v_addc_co_u32_e32 v69, vcc, 0, v91, vcc
	global_load_dwordx4 v[138:141], v[64:65], off
	global_load_dwordx4 v[142:145], v[68:69], off
	v_or_b32_e32 v68, 9, v82
	v_or_b32_e32 v64, 16, v82
	v_ashrrev_i32_e32 v69, 31, v68
	v_ashrrev_i32_e32 v65, 31, v64
	v_lshl_add_u64 v[86:87], v[68:69], 2, s[6:7]
	v_lshl_add_u64 v[88:89], v[64:65], 2, s[6:7]
	global_load_dwordx3 v[206:208], v[86:87], off
	global_load_dword v65, v[88:89], off
	v_add_co_u32_e32 v86, vcc, s69, v88
	v_add_f32_e32 v66, v85, v72
	s_nop 0
	v_addc_co_u32_e32 v87, vcc, 0, v89, vcc
	v_add_co_u32_e32 v90, vcc, s70, v88
	v_fmamk_f32 v70, v70, 0x3a800000, v118
	s_nop 0
	v_addc_co_u32_e32 v91, vcc, 0, v89, vcc
	global_load_dwordx4 v[146:149], v[86:87], off
	global_load_dwordx4 v[150:153], v[90:91], off
	v_add_co_u32_e32 v86, vcc, s71, v88
	v_fmamk_f32 v71, v71, 0x3a800000, v118
	s_nop 0
	v_addc_co_u32_e32 v87, vcc, 0, v89, vcc
	v_add_co_u32_e32 v90, vcc, s72, v88
	v_rsq_f32_e32 v71, v71
	s_nop 0
	v_addc_co_u32_e32 v91, vcc, 0, v89, vcc
	global_load_dwordx4 v[154:157], v[86:87], off
	global_load_dwordx4 v[158:161], v[90:91], off
	v_add_co_u32_e32 v86, vcc, s73, v88
	v_or_b32_e32 v85, 10, v82
	s_nop 0
	v_addc_co_u32_e32 v87, vcc, 0, v89, vcc
	v_add_co_u32_e32 v90, vcc, s74, v88
	v_or_b32_e32 v121, 18, v82
	s_nop 0
	v_addc_co_u32_e32 v91, vcc, 0, v89, vcc
	global_load_dwordx4 v[162:165], v[86:87], off
	global_load_dwordx4 v[166:169], v[90:91], off
	v_add_co_u32_e32 v86, vcc, s75, v88
	v_or_b32_e32 v88, 17, v82
	s_nop 0
	v_addc_co_u32_e32 v87, vcc, 0, v89, vcc
	v_ashrrev_i32_e32 v89, 31, v88
	v_lshl_add_u64 v[90:91], v[88:89], 2, s[6:7]
	global_load_dwordx4 v[170:173], v[86:87], off
	global_load_dwordx3 v[210:212], v[90:91], off
	v_or_b32_e32 v86, 24, v82
	v_ashrrev_i32_e32 v87, 31, v86
	v_lshl_add_u64 v[90:91], v[86:87], 2, s[6:7]
	v_add_co_u32_e32 v174, vcc, s69, v90
	v_or_b32_e32 v87, 11, v82
	s_nop 0
	v_addc_co_u32_e32 v175, vcc, 0, v91, vcc
	v_add_co_u32_e32 v178, vcc, s70, v90
	global_load_dword v69, v[90:91], off
	s_nop 0
	global_load_dwordx4 v[174:177], v[174:175], off
	v_addc_co_u32_e32 v179, vcc, 0, v91, vcc
	v_add_co_u32_e32 v182, vcc, s71, v90
	s_waitcnt vmcnt(16)
	v_add_f32_e32 v67, v122, v126
	v_addc_co_u32_e32 v183, vcc, 0, v91, vcc
	v_add_co_u32_e32 v186, vcc, s72, v90
	global_load_dwordx4 v[178:181], v[178:179], off
	s_nop 0
	global_load_dwordx4 v[182:185], v[182:183], off
	v_addc_co_u32_e32 v187, vcc, 0, v91, vcc
	v_add_co_u32_e32 v190, vcc, s73, v90
	v_add_f32_e32 v66, v66, v67
	s_nop 0
	v_addc_co_u32_e32 v191, vcc, 0, v91, vcc
	v_add_co_u32_e32 v194, vcc, s74, v90
	global_load_dwordx4 v[186:189], v[186:187], off
	s_nop 0
	global_load_dwordx4 v[190:193], v[190:191], off
	v_addc_co_u32_e32 v195, vcc, 0, v91, vcc
	v_add_co_u32_e32 v90, vcc, s75, v90
	s_waitcnt vmcnt(18)
	v_add_f32_e32 v67, v130, v134
	v_addc_co_u32_e32 v91, vcc, 0, v91, vcc
	global_load_dwordx4 v[194:197], v[194:195], off
	s_nop 0
	global_load_dwordx4 v[202:205], v[90:91], off
	s_waitcnt vmcnt(18)
	v_add_f32_e32 v72, v138, v142
	v_add_f32_e32 v67, v67, v72
	v_add_f32_e32 v72, v66, v67
	s_waitcnt vmcnt(17)
	v_add_f32_e32 v66, v206, v73
	v_add_f32_e32 v67, v123, v127
	v_add_f32_e32 v66, v66, v67
	v_add_f32_e32 v67, v131, v135
	v_add_f32_e32 v73, v139, v143
	v_add_f32_e32 v67, v67, v73
	v_add_f32_e32 v73, v66, v67
	v_add_f32_e32 v66, v207, v74
	v_add_f32_e32 v67, v124, v128
	v_add_f32_e32 v66, v66, v67
	v_add_f32_e32 v67, v132, v136
	v_add_f32_e32 v74, v140, v144
	v_add_f32_e32 v67, v67, v74
	v_add_f32_e32 v74, v66, v67
	v_add_f32_e32 v66, v208, v75
	v_add_f32_e32 v67, v125, v129
	v_or_b32_e32 v90, 25, v82
	v_add_f32_e32 v66, v66, v67
	v_add_f32_e32 v67, v133, v137
	v_add_f32_e32 v75, v141, v145
	v_ashrrev_i32_e32 v91, 31, v90
	v_add_f32_e32 v67, v67, v75
	v_lshl_add_u64 v[214:215], v[90:91], 2, s[6:7]
	v_add_f32_e32 v75, v66, v67
	s_waitcnt vmcnt(15)
	v_add_f32_e32 v65, v65, v146
	s_waitcnt vmcnt(13)
	v_add_f32_e32 v66, v150, v154
	global_load_dwordx3 v[214:216], v[214:215], off
	v_add_f32_e32 v65, v65, v66
	s_waitcnt vmcnt(12)
	v_add_f32_e32 v66, v158, v162
	v_add_f32_e32 v123, v152, v156
	v_add_f32_e32 v125, v153, v157
	v_fmamk_f32 v72, v72, 0x3a800000, v118
	v_fmamk_f32 v73, v73, 0x3a800000, v118
	v_fmamk_f32 v74, v74, 0x3a800000, v118
	v_fmamk_f32 v75, v75, 0x3a800000, v118
	v_rsq_f32_e32 v72, v72
	s_waitcnt vmcnt(10)
	v_add_f32_e32 v67, v166, v170
	v_add_f32_e32 v66, v66, v67
	v_add_f32_e32 v89, v65, v66
	s_waitcnt vmcnt(9)
	v_add_f32_e32 v65, v210, v147
	v_add_f32_e32 v66, v151, v155
	v_add_f32_e32 v65, v65, v66
	v_add_f32_e32 v66, v159, v163
	v_add_f32_e32 v67, v167, v171
	v_add_f32_e32 v66, v66, v67
	v_add_f32_e32 v91, v65, v66
	v_add_f32_e32 v65, v211, v148
	v_add_f32_e32 v65, v65, v123
	v_add_f32_e32 v123, v160, v164
	v_add_f32_e32 v124, v168, v172
	v_add_f32_e32 v123, v123, v124
	v_add_f32_e32 v123, v65, v123
	v_add_f32_e32 v65, v212, v149
	v_or_b32_e32 v66, s58, v92
	v_add_f32_e32 v65, v65, v125
	v_add_f32_e32 v125, v161, v165
	v_add_f32_e32 v126, v169, v173
	v_ashrrev_i32_e32 v67, 31, v66
	v_add_f32_e32 v125, v125, v126
	s_waitcnt vmcnt(7)
	v_add_f32_e32 v69, v69, v174
	s_waitcnt vmcnt(5)
	v_add_f32_e32 v126, v178, v182
	v_lshl_add_u64 v[66:67], v[66:67], 2, s[60:61]
	v_add_f32_e32 v69, v69, v126
	global_load_dword v122, v[66:67], off
	v_add_f32_e32 v125, v65, v125
	global_load_dword v65, v[66:67], off offset:128
	v_add_f32_e32 v128, v179, v183
	v_add_f32_e32 v130, v180, v184
	s_waitcnt vmcnt(5)
	v_add_f32_e32 v126, v186, v190
	v_add_f32_e32 v132, v181, v185
	v_fmamk_f32 v89, v89, 0x3a800000, v118
	v_fmamk_f32 v91, v91, 0x3a800000, v118
	v_fmamk_f32 v123, v123, 0x3a800000, v118
	v_fmamk_f32 v125, v125, 0x3a800000, v118
	v_rsq_f32_e32 v73, v73
	v_rsq_f32_e32 v74, v74
	s_waitcnt vmcnt(3)
	v_add_f32_e32 v127, v194, v202
	v_add_f32_e32 v126, v126, v127
	v_add_f32_e32 v69, v69, v126
	global_load_dword v126, v[66:67], off offset:256
	v_add_f32_e32 v129, v195, v203
	global_load_dword v66, v[66:67], off offset:384
	v_add_f32_e32 v131, v196, v204
	v_add_f32_e32 v133, v197, v205
	v_rsq_f32_e32 v67, v70
	v_fmamk_f32 v70, v209, 0x3a800000, v118
	v_fmamk_f32 v69, v69, 0x3a800000, v118
	v_rsq_f32_e32 v70, v70
	v_rsq_f32_e32 v75, v75
	v_rsq_f32_e32 v89, v89
	v_rsq_f32_e32 v91, v91
	v_rsq_f32_e32 v123, v123
	v_rsq_f32_e32 v125, v125
	v_rsq_f32_e32 v69, v69
	v_or_b32_e32 v124, 19, v82
	s_waitcnt vmcnt(4)
	v_add_f32_e32 v127, v214, v175
	v_add_f32_e32 v127, v127, v128
	v_add_f32_e32 v128, v187, v191
	v_add_f32_e32 v128, v128, v129
	v_add_f32_e32 v129, v215, v176
	v_add_f32_e32 v129, v129, v130
	v_add_f32_e32 v130, v188, v192
	v_add_f32_e32 v130, v130, v131
	v_add_f32_e32 v131, v216, v177
	v_add_f32_e32 v131, v131, v132
	v_add_f32_e32 v132, v189, v193
	v_add_f32_e32 v132, v132, v133
	v_add_f32_e32 v127, v127, v128
	v_add_f32_e32 v129, v129, v130
	v_add_f32_e32 v131, v131, v132
	v_fmamk_f32 v132, v213, 0x3a800000, v118
	v_fmamk_f32 v127, v127, 0x3a800000, v118
	v_fmamk_f32 v129, v129, 0x3a800000, v118
	v_fmamk_f32 v131, v131, 0x3a800000, v118
	v_rsq_f32_e32 v132, v132
	v_rsq_f32_e32 v127, v127
	v_rsq_f32_e32 v129, v129
	v_rsq_f32_e32 v131, v131
	v_or_b32_e32 v128, 26, v82
	v_or_b32_e32 v130, 27, v82
	s_waitcnt vmcnt(3)
	v_fma_f32 v48, v48, v67, v122
	v_fma_f32 v49, v49, v70, v122
	s_waitcnt vmcnt(2)
	v_fma_f32 v32, v32, v67, v65
	v_fma_f32 v33, v33, v70, v65
	v_fma_f32 v34, v34, v132, v65
	v_fma_f32 v35, v35, v71, v65
	v_fma_f32 v36, v36, v72, v65
	v_fma_f32 v37, v37, v73, v65
	v_fma_f32 v38, v38, v74, v65
	v_fma_f32 v39, v39, v75, v65
	v_fma_f32 v40, v40, v89, v65
	v_fma_f32 v41, v41, v91, v65
	v_fma_f32 v42, v42, v123, v65
	v_fma_f32 v43, v43, v125, v65
	v_fma_f32 v44, v44, v69, v65
	v_fma_f32 v45, v45, v127, v65
	v_fma_f32 v46, v46, v129, v65
	v_fmac_f32_e32 v65, v47, v131
	s_waitcnt vmcnt(0)
	v_fma_f32 v47, v0, v67, v66
	v_mul_f32_e32 v0, 0xbfb8aa3b, v48
	v_fma_f32 v16, v16, v67, v126
	v_fma_f32 v67, v2, v132, v66
	v_exp_f32_e32 v2, v0
	v_fma_f32 v50, v50, v132, v122
	v_fma_f32 v51, v51, v71, v122
	v_fma_f32 v52, v52, v72, v122
	v_add_f32_e32 v2, 1.0, v2
	v_rcp_f32_e32 v2, v2
	v_fma_f32 v53, v53, v73, v122
	v_fma_f32 v54, v54, v74, v122
	v_fma_f32 v55, v55, v75, v122
	v_fma_f32 v56, v56, v89, v122
	v_fma_f32 v57, v57, v91, v122
	v_fma_f32 v58, v58, v123, v122
	v_fma_f32 v59, v59, v125, v122
	v_fma_f32 v60, v60, v69, v122
	v_fma_f32 v61, v61, v127, v122
	v_fma_f32 v62, v62, v129, v122
	v_fmac_f32_e32 v122, v63, v131
	v_fma_f32 v17, v17, v70, v126
	v_fma_f32 v63, v1, v70, v66
	v_fma_f32 v70, v3, v71, v66
	v_mul_f32_e32 v3, 0xbfb8aa3b, v49
	v_exp_f32_e32 v3, v3
	v_mul_f32_e32 v2, v48, v2
	v_mul_f32_e32 v2, v16, v2
	v_fma_f32 v19, v19, v71, v126
	v_fma_f32 v71, v4, v72, v66
	v_cvt_pk_bf16_f32 v4, v2, s0
	v_add_f32_e32 v2, 1.0, v3
	v_fma_f32 v20, v20, v72, v126
	v_fma_f32 v72, v5, v73, v66
	v_lshl_or_b32 v0, s76, 6, v92
	v_rcp_f32_e32 v5, v2
	v_ashrrev_i32_e32 v1, 31, v0
	v_lshl_add_u64 v[0:1], v[0:1], 1, s[8:9]
	v_mad_i64_i32 v[2:3], s[58:59], v82, s68, v[0:1]
	global_store_short v[2:3], v4, off sc1
	v_mul_f32_e32 v4, v49, v5
	v_mul_f32_e32 v5, 0xbfb8aa3b, v50
	v_fma_f32 v21, v21, v73, v126
	v_fma_f32 v73, v6, v74, v66
	v_exp_f32_e32 v6, v5
	v_mul_f32_e32 v4, v17, v4
	v_fma_f32 v22, v22, v74, v126
	v_fma_f32 v74, v7, v75, v66
	v_add_f32_e32 v6, 1.0, v6
	v_cvt_pk_bf16_f32 v7, v4, s0
	v_mad_i64_i32 v[4:5], s[58:59], v120, s68, v[0:1]
	v_rcp_f32_e32 v6, v6
	global_store_short v[4:5], v7, off sc1
	v_mul_f32_e32 v7, 0xbfb8aa3b, v51
	v_exp_f32_e32 v7, v7
	v_fma_f32 v18, v18, v132, v126
	v_mul_f32_e32 v6, v50, v6
	v_mul_f32_e32 v6, v18, v6
	v_fma_f32 v23, v23, v75, v126
	v_fma_f32 v75, v8, v89, v66
	v_cvt_pk_bf16_f32 v8, v6, s0
	v_add_f32_e32 v6, 1.0, v7
	v_fma_f32 v24, v24, v89, v126
	v_fma_f32 v89, v9, v91, v66
	v_rcp_f32_e32 v9, v6
	v_mad_i64_i32 v[6:7], s[58:59], v119, s68, v[0:1]
	global_store_short v[6:7], v8, off sc1
	v_mul_f32_e32 v8, v51, v9
	v_mul_f32_e32 v9, 0xbfb8aa3b, v52
	v_fma_f32 v25, v25, v91, v126
	v_fma_f32 v91, v10, v123, v66
	v_exp_f32_e32 v10, v9
	v_mul_f32_e32 v8, v19, v8
	v_fma_f32 v26, v26, v123, v126
	v_fma_f32 v123, v11, v125, v66
	v_add_f32_e32 v10, 1.0, v10
	v_cvt_pk_bf16_f32 v11, v8, s0
	v_mad_i64_i32 v[8:9], s[58:59], v83, s68, v[0:1]
	v_rcp_f32_e32 v10, v10
	global_store_short v[8:9], v11, off sc1
	v_mul_f32_e32 v11, 0xbfb8aa3b, v53
	v_exp_f32_e32 v11, v11
	v_mul_f32_e32 v10, v52, v10
	v_mul_f32_e32 v10, v20, v10
	v_fma_f32 v28, v28, v69, v126
	v_fma_f32 v69, v12, v69, v66
	v_cvt_pk_bf16_f32 v12, v10, s0
	v_add_f32_e32 v10, 1.0, v11
	v_fma_f32 v27, v27, v125, v126
	v_fma_f32 v125, v13, v127, v66
	v_rcp_f32_e32 v13, v10
	v_mad_i64_i32 v[10:11], s[58:59], v84, s68, v[0:1]
	global_store_short v[10:11], v12, off sc1
	v_mul_f32_e32 v12, v53, v13
	v_mul_f32_e32 v13, 0xbfb8aa3b, v54
	v_fma_f32 v29, v29, v127, v126
	v_fma_f32 v127, v14, v129, v66
	v_exp_f32_e32 v14, v13
	v_mul_f32_e32 v12, v21, v12
	v_fmac_f32_e32 v66, v15, v131
	v_cvt_pk_bf16_f32 v15, v12, s0
	v_add_f32_e32 v14, 1.0, v14
	v_mad_i64_i32 v[12:13], s[58:59], v68, s68, v[0:1]
	v_rcp_f32_e32 v14, v14
	global_store_short v[12:13], v15, off sc1
	v_mul_f32_e32 v15, 0xbfb8aa3b, v55
	v_exp_f32_e32 v15, v15
	v_mul_f32_e32 v14, v54, v14
	v_mul_f32_e32 v14, v22, v14
	v_cvt_pk_bf16_f32 v16, v14, s0
	v_add_f32_e32 v14, 1.0, v15
	v_rcp_f32_e32 v17, v14
	v_mad_i64_i32 v[14:15], s[58:59], v85, s68, v[0:1]
	global_store_short v[14:15], v16, off sc1
	v_mul_f32_e32 v16, v55, v17
	v_mul_f32_e32 v17, 0xbfb8aa3b, v56
	v_exp_f32_e32 v18, v17
	v_mul_f32_e32 v16, v23, v16
	v_cvt_pk_bf16_f32 v19, v16, s0
	v_mad_i64_i32 v[16:17], s[58:59], v87, s68, v[0:1]
	v_add_f32_e32 v18, 1.0, v18
	v_rcp_f32_e32 v18, v18
	global_store_short v[16:17], v19, off sc1
	v_mul_f32_e32 v19, 0xbfb8aa3b, v57
	v_exp_f32_e32 v19, v19
	v_mul_f32_e32 v18, v56, v18
	v_mul_f32_e32 v18, v24, v18
	v_cvt_pk_bf16_f32 v20, v18, s0
	v_add_f32_e32 v18, 1.0, v19
	v_rcp_f32_e32 v21, v18
	v_mad_i64_i32 v[18:19], s[58:59], v64, s68, v[0:1]
	global_store_short v[18:19], v20, off sc1
	v_mul_f32_e32 v20, v57, v21
	v_mul_f32_e32 v21, 0xbfb8aa3b, v58
	v_exp_f32_e32 v22, v21
	v_mul_f32_e32 v20, v25, v20
	v_cvt_pk_bf16_f32 v23, v20, s0
	v_mad_i64_i32 v[20:21], s[58:59], v88, s68, v[0:1]
	v_add_f32_e32 v22, 1.0, v22
	v_rcp_f32_e32 v22, v22
	global_store_short v[20:21], v23, off sc1
	v_mul_f32_e32 v23, 0xbfb8aa3b, v59
	v_exp_f32_e32 v23, v23
	v_mul_f32_e32 v22, v58, v22
	v_mul_f32_e32 v22, v26, v22
	v_cvt_pk_bf16_f32 v24, v22, s0
	v_add_f32_e32 v22, 1.0, v23
	v_rcp_f32_e32 v25, v22
	v_mad_i64_i32 v[22:23], s[58:59], v121, s68, v[0:1]
	global_store_short v[22:23], v24, off sc1
	v_mul_f32_e32 v24, v59, v25
	v_mul_f32_e32 v25, 0xbfb8aa3b, v60
	v_exp_f32_e32 v26, v25
	v_mul_f32_e32 v24, v27, v24
	v_cvt_pk_bf16_f32 v27, v24, s0
	v_mad_i64_i32 v[24:25], s[58:59], v124, s68, v[0:1]
	v_add_f32_e32 v26, 1.0, v26
	v_rcp_f32_e32 v26, v26
	global_store_short v[24:25], v27, off sc1
	v_mul_f32_e32 v27, 0xbfb8aa3b, v61
	v_exp_f32_e32 v27, v27
	v_mul_f32_e32 v26, v60, v26
	v_mul_f32_e32 v26, v28, v26
	v_cvt_pk_bf16_f32 v28, v26, s0
	v_add_f32_e32 v26, 1.0, v27
	v_fma_f32 v30, v30, v129, v126
	v_fmac_f32_e32 v126, v31, v131
	v_rcp_f32_e32 v31, v26
	v_mad_i64_i32 v[26:27], s[58:59], v86, s68, v[0:1]
	global_store_short v[26:27], v28, off sc1
	v_mul_f32_e32 v28, v61, v31
	v_mul_f32_e32 v28, v29, v28
	v_mul_f32_e32 v29, 0xbfb8aa3b, v62
	v_exp_f32_e32 v31, v29
	v_cvt_pk_bf16_f32 v48, v28, s0
	v_mad_i64_i32 v[28:29], s[58:59], v90, s68, v[0:1]
	v_add_f32_e32 v31, 1.0, v31
	v_rcp_f32_e32 v31, v31
	global_store_short v[28:29], v48, off sc1
	v_mul_f32_e32 v48, 0xbfb8aa3b, v122
	v_exp_f32_e32 v48, v48
	v_mul_f32_e32 v31, v62, v31
	v_mul_f32_e32 v30, v30, v31
	v_cvt_pk_bf16_f32 v49, v30, s0
	v_add_f32_e32 v30, 1.0, v48
	v_rcp_f32_e32 v48, v30
	v_mad_i64_i32 v[30:31], s[58:59], v128, s68, v[0:1]
	global_store_short v[30:31], v49, off sc1
	v_mul_f32_e32 v49, 0xbfb8aa3b, v32
	v_exp_f32_e32 v49, v49
	v_mul_f32_e32 v48, v122, v48
	v_mul_f32_e32 v48, v126, v48
	v_cvt_pk_bf16_f32 v48, v48, s0
	v_mad_i64_i32 v[0:1], s[58:59], v130, s68, v[0:1]
	v_add_f32_e32 v49, 1.0, v49
	v_rcp_f32_e32 v49, v49
	global_store_short v[0:1], v48, off sc1
	v_mul_f32_e32 v48, 0xbfb8aa3b, v33
	v_exp_f32_e32 v48, v48
	v_mul_f32_e32 v32, v32, v49
	v_mul_f32_e32 v32, v47, v32
	v_cvt_pk_bf16_f32 v32, v32, s0
	v_add_f32_e32 v47, 1.0, v48
	v_rcp_f32_e32 v47, v47
	global_store_short v[2:3], v32, off offset:64 sc1
	v_mul_f32_e32 v2, 0xbfb8aa3b, v34
	v_exp_f32_e32 v2, v2
	v_mul_f32_e32 v3, v33, v47
	v_mul_f32_e32 v3, v63, v3
	v_cvt_pk_bf16_f32 v3, v3, s0
	global_store_short v[4:5], v3, off offset:64 sc1
	v_mul_f32_e32 v3, 0xbfb8aa3b, v35
	v_exp_f32_e32 v3, v3
	v_add_f32_e32 v2, 1.0, v2
	v_rcp_f32_e32 v2, v2
	v_mul_f32_e32 v4, 0xbfb8aa3b, v46
	v_add_f32_e32 v3, 1.0, v3
	v_rcp_f32_e32 v3, v3
	v_mul_f32_e32 v2, v34, v2
	v_mul_f32_e32 v2, v67, v2
	v_cvt_pk_bf16_f32 v2, v2, s0
	global_store_short v[6:7], v2, off offset:64 sc1
	v_mul_f32_e32 v2, 0xbfb8aa3b, v36
	v_mul_f32_e32 v3, v35, v3
	v_exp_f32_e32 v2, v2
	v_mul_f32_e32 v3, v70, v3
	v_cvt_pk_bf16_f32 v3, v3, s0
	global_store_short v[8:9], v3, off offset:64 sc1
	v_mul_f32_e32 v3, 0xbfb8aa3b, v37
	v_exp_f32_e32 v3, v3
	v_add_f32_e32 v2, 1.0, v2
	v_rcp_f32_e32 v2, v2
	v_exp_f32_e32 v4, v4
	v_add_f32_e32 v3, 1.0, v3
	v_rcp_f32_e32 v3, v3
	v_mul_f32_e32 v2, v36, v2
	v_mul_f32_e32 v2, v71, v2
	v_cvt_pk_bf16_f32 v2, v2, s0
	global_store_short v[10:11], v2, off offset:64 sc1
	v_mul_f32_e32 v2, 0xbfb8aa3b, v38
	v_mul_f32_e32 v3, v37, v3
	v_exp_f32_e32 v2, v2
	v_mul_f32_e32 v3, v72, v3
	v_cvt_pk_bf16_f32 v3, v3, s0
	global_store_short v[12:13], v3, off offset:64 sc1
	v_mul_f32_e32 v3, 0xbfb8aa3b, v39
	v_exp_f32_e32 v3, v3
	v_add_f32_e32 v2, 1.0, v2
	v_rcp_f32_e32 v2, v2
	v_add_f32_e32 v3, 1.0, v3
	v_rcp_f32_e32 v3, v3
	v_mul_f32_e32 v2, v38, v2
	v_mul_f32_e32 v2, v73, v2
	v_cvt_pk_bf16_f32 v2, v2, s0
	global_store_short v[14:15], v2, off offset:64 sc1
	v_mul_f32_e32 v2, 0xbfb8aa3b, v40
	v_mul_f32_e32 v3, v39, v3
	v_exp_f32_e32 v2, v2
	v_mul_f32_e32 v3, v74, v3
	v_cvt_pk_bf16_f32 v3, v3, s0
	global_store_short v[16:17], v3, off offset:64 sc1
	v_mul_f32_e32 v3, 0xbfb8aa3b, v41
	v_exp_f32_e32 v3, v3
	v_add_f32_e32 v2, 1.0, v2
	v_rcp_f32_e32 v2, v2
	v_add_f32_e32 v3, 1.0, v3
	v_rcp_f32_e32 v3, v3
	v_mul_f32_e32 v2, v40, v2
	v_mul_f32_e32 v2, v75, v2
	v_cvt_pk_bf16_f32 v2, v2, s0
	global_store_short v[18:19], v2, off offset:64 sc1
	v_mul_f32_e32 v2, 0xbfb8aa3b, v42
	v_mul_f32_e32 v3, v41, v3
	v_exp_f32_e32 v2, v2
	v_mul_f32_e32 v3, v89, v3
	v_cvt_pk_bf16_f32 v3, v3, s0
	global_store_short v[20:21], v3, off offset:64 sc1
	v_mul_f32_e32 v3, 0xbfb8aa3b, v43
	v_exp_f32_e32 v3, v3
	v_add_f32_e32 v2, 1.0, v2
	v_rcp_f32_e32 v2, v2
	v_add_f32_e32 v3, 1.0, v3
	v_rcp_f32_e32 v3, v3
	v_mul_f32_e32 v2, v42, v2
	v_mul_f32_e32 v2, v91, v2
	v_cvt_pk_bf16_f32 v2, v2, s0
	global_store_short v[22:23], v2, off offset:64 sc1
	v_mul_f32_e32 v2, 0xbfb8aa3b, v44
	v_mul_f32_e32 v3, v43, v3
	v_exp_f32_e32 v2, v2
	v_mul_f32_e32 v3, v123, v3
	v_cvt_pk_bf16_f32 v3, v3, s0
	global_store_short v[24:25], v3, off offset:64 sc1
	v_mul_f32_e32 v3, 0xbfb8aa3b, v45
	v_exp_f32_e32 v3, v3
	v_add_f32_e32 v2, 1.0, v2
	v_rcp_f32_e32 v2, v2
	v_add_f32_e32 v3, 1.0, v3
	v_rcp_f32_e32 v3, v3
	v_mul_f32_e32 v2, v44, v2
	v_mul_f32_e32 v2, v69, v2
	v_cvt_pk_bf16_f32 v2, v2, s0
	global_store_short v[26:27], v2, off offset:64 sc1
	v_mul_f32_e32 v2, v45, v3
	v_add_f32_e32 v3, 1.0, v4
	v_mul_f32_e32 v4, 0xbfb8aa3b, v65
	v_rcp_f32_e32 v3, v3
	v_exp_f32_e32 v4, v4
	v_mul_f32_e32 v2, v125, v2
	v_cvt_pk_bf16_f32 v2, v2, s0
	global_store_short v[28:29], v2, off offset:64 sc1
	v_mul_f32_e32 v2, v46, v3
	v_add_f32_e32 v3, 1.0, v4
	v_rcp_f32_e32 v3, v3
	v_mul_f32_e32 v2, v127, v2
	v_cvt_pk_bf16_f32 v2, v2, s0
	global_store_short v[30:31], v2, off offset:64 sc1
	v_mul_f32_e32 v2, v65, v3
	v_mul_f32_e32 v2, v66, v2
	v_cvt_pk_bf16_f32 v2, v2, s0
	global_store_short v[0:1], v2, off offset:64 sc1
	s_cbranch_scc1 .LBB0_759

.Lmap_done_0:
	s_lshl_b32 s60, s4, 7
	s_lshl_b32 s58, s76, 7
	s_ashr_i32 s61, s60, 31
	s_ashr_i32 s59, s58, 31
	s_lshl_b64 s[62:63], s[60:61], 11
	s_lshl_b64 s[64:65], s[58:59], 11
	s_cmp_eq_u32 s39, 1
	s_cbranch_scc1 .Lgk_pfhead_p7
	s_lshl_b32 s38, s60, 11
	s_add_u32 s18, s14, s38
	s_addc_u32 s19, s15, 0
	s_add_u32 s18, s18, 0x679f000
	s_addc_u32 s19, s19, 0
	s_add_u32 s20, s18, 0x10000
	s_addc_u32 s21, s19, 0
	s_add_u32 s22, s20, 0x10000
	s_addc_u32 s23, s21, 0
	s_add_u32 s24, s22, 0x10000
	s_addc_u32 s25, s23, 0
	s_lshl_b32 s38, s58, 11
	s_add_u32 s26, s14, s38
	s_addc_u32 s27, s15, 0
	s_add_u32 s26, s26, 0x19a0000
	s_addc_u32 s27, s27, 0
	s_add_u32 s28, s26, 0x10000
	s_addc_u32 s29, s27, 0
	s_add_u32 s30, s28, 0x10000
	s_addc_u32 s31, s29, 0
	s_add_u32 s34, s30, 0x10000
	s_addc_u32 s35, s31, 0
	v_readfirstlane_b32 s36, v94
	v_mov_b32_e32 v254, v76
	s_mov_b32 m0, s36
	s_nop 0
	global_load_lds_dwordx4 v254, s[18:19]
	s_add_u32 m0, m0, 0x1000
	s_nop 0
	global_load_lds_dwordx4 v254, s[20:21]
	s_add_u32 m0, m0, 0x1000
	s_nop 0
	global_load_lds_dwordx4 v254, s[22:23]
	s_add_u32 m0, m0, 0x1000
	s_nop 0
	global_load_lds_dwordx4 v254, s[24:25]
	s_add_u32 m0, m0, 0x1000
	s_nop 0
	global_load_lds_dwordx4 v254, s[26:27]
	s_add_u32 m0, m0, 0x1000
	s_nop 0
	global_load_lds_dwordx4 v254, s[28:29]
	s_add_u32 m0, m0, 0x1000
	s_nop 0
	global_load_lds_dwordx4 v254, s[30:31]
	s_add_u32 m0, m0, 0x1000
	s_nop 0
	global_load_lds_dwordx4 v254, s[34:35]
	v_add_u32_e32 v254, 0x80, v254
	s_add_u32 m0, s36, 0x8000
	s_nop 0
	global_load_lds_dwordx4 v254, s[18:19]
	s_add_u32 m0, m0, 0x1000
	s_nop 0
	global_load_lds_dwordx4 v254, s[20:21]
	s_add_u32 m0, m0, 0x1000
	s_nop 0
	global_load_lds_dwordx4 v254, s[22:23]
	s_add_u32 m0, m0, 0x1000
	s_nop 0
	global_load_lds_dwordx4 v254, s[24:25]
	s_add_u32 m0, m0, 0x1000
	s_nop 0
	global_load_lds_dwordx4 v254, s[26:27]
	s_add_u32 m0, m0, 0x1000
	s_nop 0
	global_load_lds_dwordx4 v254, s[28:29]
	s_add_u32 m0, m0, 0x1000
	s_nop 0
	global_load_lds_dwordx4 v254, s[30:31]
	s_add_u32 m0, m0, 0x1000
	s_nop 0
	global_load_lds_dwordx4 v254, s[34:35]
	v_add_u32_e32 v254, 0x80, v254

.Lgk_loop_p7:
	s_waitcnt vmcnt(8)
	s_barrier
	ds_read_b128 v[64:67], v110
	ds_read_b128 v[68:71], v111 offset:16384
	ds_read_b128 v[72:75], v111 offset:20480
	ds_read_b128 v[82:85], v111 offset:24576
	ds_read_b128 v[86:89], v111 offset:28672
	ds_read_b128 v[120:123], v112
	ds_read_b128 v[124:127], v113 offset:16384
	ds_read_b128 v[128:131], v113 offset:20480
	ds_read_b128 v[132:135], v113 offset:24576
	ds_read_b128 v[136:139], v113 offset:28672
	ds_read_b128 v[140:143], v114
	ds_read_b128 v[218:221], v115 offset:16384
	ds_read_b128 v[222:225], v115 offset:20480
	ds_read_b128 v[226:229], v115 offset:24576
	ds_read_b128 v[230:233], v115 offset:28672
	ds_read_b128 v[234:237], v116
	ds_read_b128 v[238:241], v117 offset:16384
	ds_read_b128 v[242:245], v117 offset:20480
	ds_read_b128 v[246:249], v117 offset:24576
	ds_read_b128 v[250:253], v117 offset:28672
	s_waitcnt lgkmcnt(0)
	s_barrier
	s_mov_b32 m0, s36
	s_setprio 1
	v_mfma_f32_32x32x16_bf16 v[48:63], v[64:67], v[68:71], v[48:63]
	v_mfma_f32_32x32x16_bf16 v[32:47], v[64:67], v[72:75], v[32:47]
	global_load_lds_dwordx4 v254, s[18:19]
	s_add_u32 m0, m0, 0x1000
	v_mfma_f32_32x32x16_bf16 v[16:31], v[64:67], v[82:85], v[16:31]
	v_mfma_f32_32x32x16_bf16 v[0:15], v[64:67], v[86:89], v[0:15]
	global_load_lds_dwordx4 v254, s[20:21]
	s_add_u32 m0, m0, 0x1000
	v_mfma_f32_32x32x16_bf16 v[48:63], v[120:123], v[124:127], v[48:63]
	v_mfma_f32_32x32x16_bf16 v[32:47], v[120:123], v[128:131], v[32:47]
	global_load_lds_dwordx4 v254, s[22:23]
	s_add_u32 m0, m0, 0x1000
	v_mfma_f32_32x32x16_bf16 v[16:31], v[120:123], v[132:135], v[16:31]
	v_mfma_f32_32x32x16_bf16 v[0:15], v[120:123], v[136:139], v[0:15]
	global_load_lds_dwordx4 v254, s[24:25]
	s_add_u32 m0, m0, 0x1000
	v_mfma_f32_32x32x16_bf16 v[48:63], v[140:143], v[218:221], v[48:63]
	v_mfma_f32_32x32x16_bf16 v[32:47], v[140:143], v[222:225], v[32:47]
	global_load_lds_dwordx4 v254, s[26:27]
	s_add_u32 m0, m0, 0x1000
	v_mfma_f32_32x32x16_bf16 v[16:31], v[140:143], v[226:229], v[16:31]
	v_mfma_f32_32x32x16_bf16 v[0:15], v[140:143], v[230:233], v[0:15]
	global_load_lds_dwordx4 v254, s[28:29]
	s_add_u32 m0, m0, 0x1000
	v_mfma_f32_32x32x16_bf16 v[48:63], v[234:237], v[238:241], v[48:63]
	v_mfma_f32_32x32x16_bf16 v[32:47], v[234:237], v[242:245], v[32:47]
	global_load_lds_dwordx4 v254, s[30:31]
	s_add_u32 m0, m0, 0x1000
	v_mfma_f32_32x32x16_bf16 v[16:31], v[234:237], v[246:249], v[16:31]
	v_mfma_f32_32x32x16_bf16 v[0:15], v[234:237], v[250:253], v[0:15]
	global_load_lds_dwordx4 v254, s[34:35]
	s_setprio 0
	v_add_u32_e32 v254, 0x80, v254
	s_waitcnt vmcnt(8)
	s_barrier
	ds_read_b128 v[64:67], v110 offset:32768
	ds_read_b128 v[68:71], v111 offset:49152
	ds_read_b128 v[72:75], v111 offset:53248
	ds_read_b128 v[82:85], v111 offset:57344
	ds_read_b128 v[86:89], v111 offset:61440
	ds_read_b128 v[120:123], v112 offset:32768
	ds_read_b128 v[124:127], v113 offset:49152
	ds_read_b128 v[128:131], v113 offset:53248
	ds_read_b128 v[132:135], v113 offset:57344
	ds_read_b128 v[136:139], v113 offset:61440
	ds_read_b128 v[140:143], v114 offset:32768
	ds_read_b128 v[218:221], v115 offset:49152
	ds_read_b128 v[222:225], v115 offset:53248
	ds_read_b128 v[226:229], v115 offset:57344
	ds_read_b128 v[230:233], v115 offset:61440
	ds_read_b128 v[234:237], v116 offset:32768
	ds_read_b128 v[238:241], v117 offset:49152
	ds_read_b128 v[242:245], v117 offset:53248
	ds_read_b128 v[246:249], v117 offset:57344
	ds_read_b128 v[250:253], v117 offset:61440
	s_waitcnt lgkmcnt(0)
	s_barrier
	s_add_u32 m0, s36, 0x8000
	s_setprio 1
	v_mfma_f32_32x32x16_bf16 v[48:63], v[64:67], v[68:71], v[48:63]
	v_mfma_f32_32x32x16_bf16 v[32:47], v[64:67], v[72:75], v[32:47]
	global_load_lds_dwordx4 v254, s[18:19]
	s_add_u32 m0, m0, 0x1000
	v_mfma_f32_32x32x16_bf16 v[16:31], v[64:67], v[82:85], v[16:31]
	v_mfma_f32_32x32x16_bf16 v[0:15], v[64:67], v[86:89], v[0:15]
	global_load_lds_dwordx4 v254, s[20:21]
	s_add_u32 m0, m0, 0x1000
	v_mfma_f32_32x32x16_bf16 v[48:63], v[120:123], v[124:127], v[48:63]
	v_mfma_f32_32x32x16_bf16 v[32:47], v[120:123], v[128:131], v[32:47]
	global_load_lds_dwordx4 v254, s[22:23]
	s_add_u32 m0, m0, 0x1000
	v_mfma_f32_32x32x16_bf16 v[16:31], v[120:123], v[132:135], v[16:31]
	v_mfma_f32_32x32x16_bf16 v[0:15], v[120:123], v[136:139], v[0:15]
	global_load_lds_dwordx4 v254, s[24:25]
	s_add_u32 m0, m0, 0x1000
	v_mfma_f32_32x32x16_bf16 v[48:63], v[140:143], v[218:221], v[48:63]
	v_mfma_f32_32x32x16_bf16 v[32:47], v[140:143], v[222:225], v[32:47]
	global_load_lds_dwordx4 v254, s[26:27]
	s_add_u32 m0, m0, 0x1000
	v_mfma_f32_32x32x16_bf16 v[16:31], v[140:143], v[226:229], v[16:31]
	v_mfma_f32_32x32x16_bf16 v[0:15], v[140:143], v[230:233], v[0:15]
	global_load_lds_dwordx4 v254, s[28:29]
	s_add_u32 m0, m0, 0x1000
	v_mfma_f32_32x32x16_bf16 v[48:63], v[234:237], v[238:241], v[48:63]
	v_mfma_f32_32x32x16_bf16 v[32:47], v[234:237], v[242:245], v[32:47]
	global_load_lds_dwordx4 v254, s[30:31]
	s_add_u32 m0, m0, 0x1000
	v_mfma_f32_32x32x16_bf16 v[16:31], v[234:237], v[246:249], v[16:31]
	v_mfma_f32_32x32x16_bf16 v[0:15], v[234:237], v[250:253], v[0:15]
	global_load_lds_dwordx4 v254, s[34:35]
	s_setprio 0
	v_add_u32_e32 v254, 0x80, v254
	s_sub_u32 s37, s37, 1
	s_cmp_lg_u32 s37, 0
	s_cbranch_scc1 .Lgk_loop_p7
	s_add_u32 s40, s3, s33
	s_cmp_gt_u32 s40, 0x15ff
	s_cbranch_scc1 .Lgk_tailplain_p7
.LBB0_755_pf_p7:
	s_and_b32 s42, s40, 7
	s_lshl_b32 s42, s42, 4
	s_bfe_u32 s43, s40, 0x60003
	s_lshr_b32 s41, s40, 9
	s_cmp_lt_u32 s41, 10
	s_cbranch_scc0 .Lmap_tail_0_pf_p7
	s_cmp_gt_u32 s41, 4
	s_cselect_b32 s50, 5, 0
	s_cselect_b32 s47, 8, 0
	s_sub_u32 s41, s41, s50
	s_lshl_b32 s41, s41, 3
	s_lshr_b32 s50, s43, 3
	s_add_u32 s50, s50, s41
	s_and_b32 s43, s43, 7
	s_add_u32 s41, s42, s47
	s_add_u32 s41, s41, s43
	s_branch .Lmap_done_0_pf_p7
.Lmap_tail_0_pf_p7:
	s_lshr_b32 s50, s43, 4
	s_add_u32 s50, s50, 40
	s_and_b32 s43, s43, 15
	s_add_u32 s41, s42, s43
.Lmap_done_0_pf_p7:
	s_lshl_b32 s44, s41, 7
	s_lshl_b32 s42, s50, 7
	s_ashr_i32 s45, s44, 31
	s_ashr_i32 s43, s42, 31
	s_lshl_b64 s[46:47], s[44:45], 11
	s_lshl_b64 s[48:49], s[42:43], 11
	s_lshl_b32 s38, s44, 11
	s_add_u32 s18, s14, s38
	s_addc_u32 s19, s15, 0
	s_add_u32 s18, s18, 0x679f000
	s_addc_u32 s19, s19, 0
	s_add_u32 s20, s18, 0x10000
	s_addc_u32 s21, s19, 0
	s_add_u32 s22, s20, 0x10000
	s_addc_u32 s23, s21, 0
	s_add_u32 s24, s22, 0x10000
	s_addc_u32 s25, s23, 0
	s_lshl_b32 s38, s42, 11
	s_add_u32 s26, s14, s38
	s_addc_u32 s27, s15, 0
	s_add_u32 s26, s26, 0x19a0000
	s_addc_u32 s27, s27, 0
	s_add_u32 s28, s26, 0x10000
	s_addc_u32 s29, s27, 0
	s_add_u32 s30, s28, 0x10000
	s_addc_u32 s31, s29, 0
	s_add_u32 s34, s30, 0x10000
	s_addc_u32 s35, s31, 0
	v_mov_b32_e32 v254, v76
	s_mov_b32 s39, 1
	s_waitcnt vmcnt(8)
	s_barrier
	ds_read_b128 v[64:67], v110
	ds_read_b128 v[68:71], v111 offset:16384
	ds_read_b128 v[72:75], v111 offset:20480
	ds_read_b128 v[82:85], v111 offset:24576
	ds_read_b128 v[86:89], v111 offset:28672
	ds_read_b128 v[120:123], v112
	ds_read_b128 v[124:127], v113 offset:16384
	ds_read_b128 v[128:131], v113 offset:20480
	ds_read_b128 v[132:135], v113 offset:24576
	ds_read_b128 v[136:139], v113 offset:28672
	ds_read_b128 v[140:143], v114
	ds_read_b128 v[218:221], v115 offset:16384
	ds_read_b128 v[222:225], v115 offset:20480
	ds_read_b128 v[226:229], v115 offset:24576
	ds_read_b128 v[230:233], v115 offset:28672
	ds_read_b128 v[234:237], v116
	ds_read_b128 v[238:241], v117 offset:16384
	ds_read_b128 v[242:245], v117 offset:20480
	ds_read_b128 v[246:249], v117 offset:24576
	ds_read_b128 v[250:253], v117 offset:28672
	s_waitcnt lgkmcnt(0)
	s_barrier
	s_mov_b32 m0, s36
	s_setprio 1
	v_mfma_f32_32x32x16_bf16 v[48:63], v[64:67], v[68:71], v[48:63]
	v_mfma_f32_32x32x16_bf16 v[32:47], v[64:67], v[72:75], v[32:47]
	global_load_lds_dwordx4 v254, s[18:19]
	s_add_u32 m0, m0, 0x1000
	v_mfma_f32_32x32x16_bf16 v[16:31], v[64:67], v[82:85], v[16:31]
	v_mfma_f32_32x32x16_bf16 v[0:15], v[64:67], v[86:89], v[0:15]
	global_load_lds_dwordx4 v254, s[20:21]
	s_add_u32 m0, m0, 0x1000
	v_mfma_f32_32x32x16_bf16 v[48:63], v[120:123], v[124:127], v[48:63]
	v_mfma_f32_32x32x16_bf16 v[32:47], v[120:123], v[128:131], v[32:47]
	global_load_lds_dwordx4 v254, s[22:23]
	s_add_u32 m0, m0, 0x1000
	v_mfma_f32_32x32x16_bf16 v[16:31], v[120:123], v[132:135], v[16:31]
	v_mfma_f32_32x32x16_bf16 v[0:15], v[120:123], v[136:139], v[0:15]
	global_load_lds_dwordx4 v254, s[24:25]
	s_add_u32 m0, m0, 0x1000
	v_mfma_f32_32x32x16_bf16 v[48:63], v[140:143], v[218:221], v[48:63]
	v_mfma_f32_32x32x16_bf16 v[32:47], v[140:143], v[222:225], v[32:47]
	global_load_lds_dwordx4 v254, s[26:27]
	s_add_u32 m0, m0, 0x1000
	v_mfma_f32_32x32x16_bf16 v[16:31], v[140:143], v[226:229], v[16:31]
	v_mfma_f32_32x32x16_bf16 v[0:15], v[140:143], v[230:233], v[0:15]
	global_load_lds_dwordx4 v254, s[28:29]
	s_add_u32 m0, m0, 0x1000
	v_mfma_f32_32x32x16_bf16 v[48:63], v[234:237], v[238:241], v[48:63]
	v_mfma_f32_32x32x16_bf16 v[32:47], v[234:237], v[242:245], v[32:47]
	global_load_lds_dwordx4 v254, s[30:31]
	s_add_u32 m0, m0, 0x1000
	v_mfma_f32_32x32x16_bf16 v[16:31], v[234:237], v[246:249], v[16:31]
	v_mfma_f32_32x32x16_bf16 v[0:15], v[234:237], v[250:253], v[0:15]
	global_load_lds_dwordx4 v254, s[34:35]
	s_setprio 0
	v_add_u32_e32 v254, 0x80, v254
	s_waitcnt vmcnt(8)
	s_barrier
	ds_read_b128 v[64:67], v110 offset:32768
	ds_read_b128 v[68:71], v111 offset:49152
	ds_read_b128 v[72:75], v111 offset:53248
	ds_read_b128 v[82:85], v111 offset:57344
	ds_read_b128 v[86:89], v111 offset:61440
	ds_read_b128 v[120:123], v112 offset:32768
	ds_read_b128 v[124:127], v113 offset:49152
	ds_read_b128 v[128:131], v113 offset:53248
	ds_read_b128 v[132:135], v113 offset:57344
	ds_read_b128 v[136:139], v113 offset:61440
	ds_read_b128 v[140:143], v114 offset:32768
	ds_read_b128 v[218:221], v115 offset:49152
	ds_read_b128 v[222:225], v115 offset:53248
	ds_read_b128 v[226:229], v115 offset:57344
	ds_read_b128 v[230:233], v115 offset:61440
	ds_read_b128 v[234:237], v116 offset:32768
	ds_read_b128 v[238:241], v117 offset:49152
	ds_read_b128 v[242:245], v117 offset:53248
	ds_read_b128 v[246:249], v117 offset:57344
	ds_read_b128 v[250:253], v117 offset:61440
	s_waitcnt lgkmcnt(0)
	s_barrier
	s_add_u32 m0, s36, 0x8000
	s_setprio 1
	v_mfma_f32_32x32x16_bf16 v[48:63], v[64:67], v[68:71], v[48:63]
	v_mfma_f32_32x32x16_bf16 v[32:47], v[64:67], v[72:75], v[32:47]
	global_load_lds_dwordx4 v254, s[18:19]
	s_add_u32 m0, m0, 0x1000
	v_mfma_f32_32x32x16_bf16 v[16:31], v[64:67], v[82:85], v[16:31]
	v_mfma_f32_32x32x16_bf16 v[0:15], v[64:67], v[86:89], v[0:15]
	global_load_lds_dwordx4 v254, s[20:21]
	s_add_u32 m0, m0, 0x1000
	v_mfma_f32_32x32x16_bf16 v[48:63], v[120:123], v[124:127], v[48:63]
	v_mfma_f32_32x32x16_bf16 v[32:47], v[120:123], v[128:131], v[32:47]
	global_load_lds_dwordx4 v254, s[22:23]
	s_add_u32 m0, m0, 0x1000
	v_mfma_f32_32x32x16_bf16 v[16:31], v[120:123], v[132:135], v[16:31]
	v_mfma_f32_32x32x16_bf16 v[0:15], v[120:123], v[136:139], v[0:15]
	global_load_lds_dwordx4 v254, s[24:25]
	s_add_u32 m0, m0, 0x1000
	v_mfma_f32_32x32x16_bf16 v[48:63], v[140:143], v[218:221], v[48:63]
	v_mfma_f32_32x32x16_bf16 v[32:47], v[140:143], v[222:225], v[32:47]
	global_load_lds_dwordx4 v254, s[26:27]
	s_add_u32 m0, m0, 0x1000
	v_mfma_f32_32x32x16_bf16 v[16:31], v[140:143], v[226:229], v[16:31]
	v_mfma_f32_32x32x16_bf16 v[0:15], v[140:143], v[230:233], v[0:15]
	global_load_lds_dwordx4 v254, s[28:29]
	s_add_u32 m0, m0, 0x1000
	v_mfma_f32_32x32x16_bf16 v[48:63], v[234:237], v[238:241], v[48:63]
	v_mfma_f32_32x32x16_bf16 v[32:47], v[234:237], v[242:245], v[32:47]
	global_load_lds_dwordx4 v254, s[30:31]
	s_add_u32 m0, m0, 0x1000
	v_mfma_f32_32x32x16_bf16 v[16:31], v[234:237], v[246:249], v[16:31]
	v_mfma_f32_32x32x16_bf16 v[0:15], v[234:237], v[250:253], v[0:15]
	global_load_lds_dwordx4 v254, s[34:35]
	s_setprio 0
	v_add_u32_e32 v254, 0x80, v254
	s_branch .LBB0_754
.Lgk_tailplain_p7:
	s_mov_b32 s39, 0
	s_waitcnt vmcnt(8)
	s_barrier
	ds_read_b128 v[64:67], v110
	ds_read_b128 v[68:71], v111 offset:16384
	ds_read_b128 v[72:75], v111 offset:20480
	ds_read_b128 v[82:85], v111 offset:24576
	ds_read_b128 v[86:89], v111 offset:28672
	ds_read_b128 v[120:123], v112
	ds_read_b128 v[124:127], v113 offset:16384
	ds_read_b128 v[128:131], v113 offset:20480
	ds_read_b128 v[132:135], v113 offset:24576
	ds_read_b128 v[136:139], v113 offset:28672
	ds_read_b128 v[140:143], v114
	ds_read_b128 v[218:221], v115 offset:16384
	ds_read_b128 v[222:225], v115 offset:20480
	ds_read_b128 v[226:229], v115 offset:24576
	ds_read_b128 v[230:233], v115 offset:28672
	ds_read_b128 v[234:237], v116
	ds_read_b128 v[238:241], v117 offset:16384
	ds_read_b128 v[242:245], v117 offset:20480
	ds_read_b128 v[246:249], v117 offset:24576
	ds_read_b128 v[250:253], v117 offset:28672
	s_waitcnt lgkmcnt(0)
	s_barrier
	s_setprio 1
	v_mfma_f32_32x32x16_bf16 v[48:63], v[64:67], v[68:71], v[48:63]
	v_mfma_f32_32x32x16_bf16 v[32:47], v[64:67], v[72:75], v[32:47]
	v_mfma_f32_32x32x16_bf16 v[16:31], v[64:67], v[82:85], v[16:31]
	v_mfma_f32_32x32x16_bf16 v[0:15], v[64:67], v[86:89], v[0:15]
	v_mfma_f32_32x32x16_bf16 v[48:63], v[120:123], v[124:127], v[48:63]
	v_mfma_f32_32x32x16_bf16 v[32:47], v[120:123], v[128:131], v[32:47]
	v_mfma_f32_32x32x16_bf16 v[16:31], v[120:123], v[132:135], v[16:31]
	v_mfma_f32_32x32x16_bf16 v[0:15], v[120:123], v[136:139], v[0:15]
	v_mfma_f32_32x32x16_bf16 v[48:63], v[140:143], v[218:221], v[48:63]
	v_mfma_f32_32x32x16_bf16 v[32:47], v[140:143], v[222:225], v[32:47]
	v_mfma_f32_32x32x16_bf16 v[16:31], v[140:143], v[226:229], v[16:31]
	v_mfma_f32_32x32x16_bf16 v[0:15], v[140:143], v[230:233], v[0:15]
	v_mfma_f32_32x32x16_bf16 v[48:63], v[234:237], v[238:241], v[48:63]
	v_mfma_f32_32x32x16_bf16 v[32:47], v[234:237], v[242:245], v[32:47]
	v_mfma_f32_32x32x16_bf16 v[16:31], v[234:237], v[246:249], v[16:31]
	v_mfma_f32_32x32x16_bf16 v[0:15], v[234:237], v[250:253], v[0:15]
	s_setprio 0
	s_waitcnt vmcnt(0)
	s_barrier
	ds_read_b128 v[64:67], v110 offset:32768
	ds_read_b128 v[68:71], v111 offset:49152
	ds_read_b128 v[72:75], v111 offset:53248
	ds_read_b128 v[82:85], v111 offset:57344
	ds_read_b128 v[86:89], v111 offset:61440
	ds_read_b128 v[120:123], v112 offset:32768
	ds_read_b128 v[124:127], v113 offset:49152
	ds_read_b128 v[128:131], v113 offset:53248
	ds_read_b128 v[132:135], v113 offset:57344
	ds_read_b128 v[136:139], v113 offset:61440
	ds_read_b128 v[140:143], v114 offset:32768
	ds_read_b128 v[218:221], v115 offset:49152
	ds_read_b128 v[222:225], v115 offset:53248
	ds_read_b128 v[226:229], v115 offset:57344
	ds_read_b128 v[230:233], v115 offset:61440
	ds_read_b128 v[234:237], v116 offset:32768
	ds_read_b128 v[238:241], v117 offset:49152
	ds_read_b128 v[242:245], v117 offset:53248
	ds_read_b128 v[246:249], v117 offset:57344
	ds_read_b128 v[250:253], v117 offset:61440
	s_waitcnt lgkmcnt(0)
	s_barrier
	s_setprio 1
	v_mfma_f32_32x32x16_bf16 v[48:63], v[64:67], v[68:71], v[48:63]
	v_mfma_f32_32x32x16_bf16 v[32:47], v[64:67], v[72:75], v[32:47]
	v_mfma_f32_32x32x16_bf16 v[16:31], v[64:67], v[82:85], v[16:31]
	v_mfma_f32_32x32x16_bf16 v[0:15], v[64:67], v[86:89], v[0:15]
	v_mfma_f32_32x32x16_bf16 v[48:63], v[120:123], v[124:127], v[48:63]
	v_mfma_f32_32x32x16_bf16 v[32:47], v[120:123], v[128:131], v[32:47]
	v_mfma_f32_32x32x16_bf16 v[16:31], v[120:123], v[132:135], v[16:31]
	v_mfma_f32_32x32x16_bf16 v[0:15], v[120:123], v[136:139], v[0:15]
	v_mfma_f32_32x32x16_bf16 v[48:63], v[140:143], v[218:221], v[48:63]
	v_mfma_f32_32x32x16_bf16 v[32:47], v[140:143], v[222:225], v[32:47]
	v_mfma_f32_32x32x16_bf16 v[16:31], v[140:143], v[226:229], v[16:31]
	v_mfma_f32_32x32x16_bf16 v[0:15], v[140:143], v[230:233], v[0:15]
	v_mfma_f32_32x32x16_bf16 v[48:63], v[234:237], v[238:241], v[48:63]
	v_mfma_f32_32x32x16_bf16 v[32:47], v[234:237], v[242:245], v[32:47]
	v_mfma_f32_32x32x16_bf16 v[16:31], v[234:237], v[246:249], v[16:31]
	v_mfma_f32_32x32x16_bf16 v[0:15], v[234:237], v[250:253], v[0:15]
	s_setprio 0
	s_branch .LBB0_754
.LBB0_759:
	s_cmp_gt_i32 s17, 8
	s_cselect_b64 s[6:7], -1, 0
	s_and_b64 s[0:1], s[0:1], s[6:7]
	s_andn2_b64 vcc, exec, s[0:1]
	s_cbranch_vccnz .LBB0_771
	s_waitcnt vmcnt(0)
	v_or_b32_e32 v0, v201, v200
	s_movk_i32 s0, 0x3ff
	v_and_or_b32 v0, v0, s0, v199
	v_cmp_eq_u32_e32 vcc, 0, v0
	s_waitcnt lgkmcnt(0)
	s_barrier
	s_and_saveexec_b64 s[0:1], vcc
	s_cbranch_execz .LBB0_770
	s_add_u32 s4, s14, 0x5be8c00
	s_addc_u32 s5, s15, 0
	s_lshl_b32 s3, s2, 1
	v_mov_b32_e32 v0, s3
	v_mov_b32_e32 v1, 0x9308
	global_store_short v0, v1, s[4:5] sc1
	s_cmp_lg_u32 s2, 0
	s_cbranch_scc1 .Lgbar_wait_7
	s_lshr_b32 s3, s33, 3
	s_bfm_b64 s[8:9], s3, 0
	s_cmpk_gt_u32 s33, 0x1ff
	s_cselect_b64 s[8:9], -1, s[8:9]
	s_mov_b64 exec, -1
	v_mbcnt_lo_u32_b32 v229, -1, 0
	v_mbcnt_hi_u32_b32 v229, -1, v229
	v_lshlrev_b32_e32 v229, 4, v229
	s_mov_b32 s10, 0x93089308
	s_mov_b64 exec, s[8:9]

.LBB0_771:
	s_cmp_lt_i32 s16, 9
	s_cselect_b64 s[4:5], -1, 0
	s_and_b64 s[0:1], s[4:5], s[6:7]
	s_andn2_b64 vcc, exec, s[0:1]
	s_cbranch_vccnz .LBB0_811
	s_ashr_i32 s0, s2, 31
	s_and_b32 s0, s0, s33
	s_add_i32 s3, s0, s2
	s_cmpk_gt_i32 s3, 0x3ff
	s_cbranch_scc1 .LBB0_811
	s_waitcnt lgkmcnt(0)
	v_lshrrev_b32_e32 v1, 5, v199
	v_bfe_u32 v5, v199, 1, 3
	v_lshrrev_b32_e32 v6, 4, v199
	v_lshrrev_b32_e32 v0, 3, v199
	v_bfe_u32 v2, v199, 5, 1
	v_xor_b32_e32 v7, v6, v199
	v_bitop3_b32 v1, v1, v5, 1 bitop3:0x6c
	v_mul_u32_u24_e32 v3, 0xb00, v0
	v_lshlrev_b32_e32 v7, 3, v7
	v_lshlrev_b32_e32 v9, 4, v1
	v_bitop3_b32 v1, v2, v5, 2 bitop3:0x36
	v_lshrrev_b32_e32 v4, 1, v199
	v_and_or_b32 v7, v7, 56, v3
	v_lshlrev_b32_e32 v11, 4, v1
	v_bitop3_b32 v1, v2, v5, 4 bitop3:0x36
	v_lshlrev_b32_e32 v64, 1, v7
	v_mov_b32_e32 v65, 0
	v_and_b32_e32 v4, 0x1e0, v4
	v_lshlrev_b32_e32 v12, 4, v1
	v_bitop3_b32 v1, v2, v5, 6 bitop3:0x36
	v_lshlrev_b32_e32 v2, 4, v1
	s_waitcnt vmcnt(25)
	v_and_or_b32 v139, v0, 4, v4
	v_lshl_add_u64 v[0:1], s[14:15], 0, v[64:65]
	s_mov_b64 s[8:9], 0x879f000
	v_and_b32_e32 v138, 31, v199
	v_lshl_add_u64 v[66:67], v[0:1], 0, s[8:9]
	s_mov_b64 s[8:9], 0x45a0000
	s_add_u32 s10, s14, 0x5c4e000
	v_lshlrev_b32_e32 v7, 4, v199
	v_or_b32_e32 v8, v4, v138
	v_lshl_add_u64 v[68:69], v[0:1], 0, s[8:9]
	s_addc_u32 s11, s15, 0
	v_bitop3_b32 v0, v6, 7, v199 bitop3:0x48
	v_lshlrev_b32_e32 v1, 1, v3
	v_lshl_add_u32 v8, v8, 7, 0
	v_lshl_add_u32 v10, v138, 7, 0
	s_add_u32 s8, s14, 0x679f000
	v_lshl_or_b32 v64, v0, 4, v1
	v_add_u32_e32 v141, 0, v7
	v_mbcnt_lo_u32_b32 v0, -1, 0
	s_mov_b32 s7, 0
	v_cmp_eq_u32_e64 s[0:1], 0, v138
	s_addc_u32 s9, s15, 0
	v_mov_b32_e32 v140, 0x1600
	v_add_u32_e32 v142, 0x4000, v141
	s_mov_b64 s[18:19], 0x2c000
	v_add_u32_e32 v143, 0x1000, v141
	s_waitcnt vmcnt(24)
	v_add_u32_e32 v144, 0x5000, v141
	s_mov_b64 s[20:21], 0x58000
	v_add_u32_e32 v145, 0x2000, v141
	v_add_u32_e32 v146, 0x6000, v141
	s_mov_b64 s[22:23], 0x84000
	v_add_u32_e32 v147, 0x3000, v141
	v_add_u32_e32 v148, 0x7000, v141
	s_mov_b64 s[24:25], 0x879f080
	s_mov_b64 s[26:27], 0x45a0080
	v_add_u32_e32 v149, 0x8000, v141
	v_add_u32_e32 v150, 0xc000, v141
	s_mov_b64 s[28:29], 0x87cb080
	v_add_u32_e32 v151, 0x9000, v141
	s_mov_b64 s[30:31], 0x45cc080
	s_waitcnt vmcnt(23)
	v_add_u32_e32 v152, 0xd000, v141
	s_mov_b64 s[34:35], 0x87f7080
	v_add_u32_e32 v153, 0xa000, v141
	s_mov_b64 s[36:37], 0x45f8080
	v_add_u32_e32 v154, 0xe000, v141
	s_mov_b64 s[38:39], 0x8823080
	v_add_u32_e32 v155, 0xb000, v141
	s_mov_b64 s[40:41], 0x4624080
	s_waitcnt vmcnt(22)
	v_add_u32_e32 v156, 0xf000, v141
	v_add_u32_e32 v157, v8, v9
	v_add_u32_e32 v158, v10, v9
	v_add_u32_e32 v159, v8, v11
	s_waitcnt vmcnt(21)
	v_add_u32_e32 v160, v10, v11
	v_add_u32_e32 v161, v8, v12
	v_add_u32_e32 v162, v10, v12
	v_add_u32_e32 v163, v8, v2
	s_waitcnt vmcnt(19)
	v_add_u32_e32 v164, v10, v2
	s_mov_b64 s[42:43], 0x879f100
	s_mov_b64 s[44:45], 0x45a0100
	s_mov_b64 s[46:47], 0x87cb100
	s_mov_b64 s[48:49], 0x45cc100
	s_mov_b64 s[50:51], 0x87f7100
	s_mov_b64 s[52:53], 0x45f8100
	s_mov_b64 s[54:55], 0x8823100
	s_mov_b64 s[56:57], 0x4624100
	s_add_i32 s66, 0, 0x12068
	v_mbcnt_hi_u32_b32 v165, -1, v0
	s_mov_b32 s39, 0
	s_branch .LBB0_775

.LBB0_775:
	s_ashr_i32 s6, s3, 31
	s_lshr_b32 s6, s6, 26
	s_add_i32 s6, s3, s6
	s_ashr_i32 s58, s6, 6
	s_andn2_b32 s6, s6, 63
	s_sub_i32 s6, s3, s6
	s_ashr_i32 s59, s6, 31
	s_lshr_b32 s59, s59, 29
	s_add_i32 s59, s6, s59
	s_ashr_i32 s64, s59, 3
	s_and_b32 s59, s59, -8
	s_lshl_b32 s58, s58, 3
	s_sub_i32 s6, s6, s59
	s_add_i32 s6, s6, s58
	s_lshl_b32 s67, s6, 7
	s_lshl_b32 s68, s64, 7
	s_waitcnt lgkmcnt(0)
	s_cmp_eq_u32 s39, 1
	s_cbranch_scc1 .Lgk_pfhead_p8
	s_mul_i32 s38, s6, 0xb0000
	s_add_u32 s18, s14, s38
	s_addc_u32 s19, s15, 0
	s_add_u32 s18, s18, 0x879f000
	s_addc_u32 s19, s19, 0
	s_add_u32 s20, s18, 0x2c000
	s_addc_u32 s21, s19, 0
	s_add_u32 s22, s20, 0x2c000
	s_addc_u32 s23, s21, 0
	s_add_u32 s24, s22, 0x2c000
	s_addc_u32 s25, s23, 0
	s_mul_i32 s38, s64, 0xb0000
	s_add_u32 s26, s14, s38
	s_addc_u32 s27, s15, 0
	s_add_u32 s26, s26, 0x45a0000
	s_addc_u32 s27, s27, 0
	s_add_u32 s28, s26, 0x2c000
	s_addc_u32 s29, s27, 0
	s_add_u32 s30, s28, 0x2c000
	s_addc_u32 s31, s29, 0
	s_add_u32 s34, s30, 0x2c000
	s_addc_u32 s35, s31, 0
	v_readfirstlane_b32 s36, v141
	v_mov_b32_e32 v254, v64
	s_mov_b32 m0, s36
	s_nop 0
	global_load_lds_dwordx4 v254, s[18:19]
	s_add_u32 m0, m0, 0x1000
	s_nop 0
	global_load_lds_dwordx4 v254, s[20:21]
	s_add_u32 m0, m0, 0x1000
	s_nop 0
	global_load_lds_dwordx4 v254, s[22:23]
	s_add_u32 m0, m0, 0x1000
	s_nop 0
	global_load_lds_dwordx4 v254, s[24:25]
	s_add_u32 m0, m0, 0x1000
	s_nop 0
	global_load_lds_dwordx4 v254, s[26:27]
	s_add_u32 m0, m0, 0x1000
	s_nop 0
	global_load_lds_dwordx4 v254, s[28:29]
	s_add_u32 m0, m0, 0x1000
	s_nop 0
	global_load_lds_dwordx4 v254, s[30:31]
	s_add_u32 m0, m0, 0x1000
	s_nop 0
	global_load_lds_dwordx4 v254, s[34:35]
	v_add_u32_e32 v254, 0x80, v254
	s_add_u32 m0, s36, 0x8000
	s_nop 0
	global_load_lds_dwordx4 v254, s[18:19]
	s_add_u32 m0, m0, 0x1000
	s_nop 0
	global_load_lds_dwordx4 v254, s[20:21]
	s_add_u32 m0, m0, 0x1000
	s_nop 0
	global_load_lds_dwordx4 v254, s[22:23]
	s_add_u32 m0, m0, 0x1000
	s_nop 0
	global_load_lds_dwordx4 v254, s[24:25]
	s_add_u32 m0, m0, 0x1000
	s_nop 0
	global_load_lds_dwordx4 v254, s[26:27]
	s_add_u32 m0, m0, 0x1000
	s_nop 0
	global_load_lds_dwordx4 v254, s[28:29]
	s_add_u32 m0, m0, 0x1000
	s_nop 0
	global_load_lds_dwordx4 v254, s[30:31]
	s_add_u32 m0, m0, 0x1000
	s_nop 0
	global_load_lds_dwordx4 v254, s[34:35]
	v_add_u32_e32 v254, 0x80, v254
.Lgk_pfhead_p8:
	v_mov_b32_e32 v48, 0
	v_mov_b32_e32 v49, 0
	v_mov_b32_e32 v50, 0
	v_mov_b32_e32 v51, 0
	v_mov_b32_e32 v52, 0
	v_mov_b32_e32 v53, 0
	v_mov_b32_e32 v54, 0
	v_mov_b32_e32 v55, 0
	v_mov_b32_e32 v56, 0
	v_mov_b32_e32 v57, 0
	v_mov_b32_e32 v58, 0
	v_mov_b32_e32 v59, 0
	v_mov_b32_e32 v60, 0
	v_mov_b32_e32 v61, 0
	v_mov_b32_e32 v62, 0
	v_mov_b32_e32 v63, 0
	v_mov_b32_e32 v32, 0
	v_mov_b32_e32 v33, 0
	v_mov_b32_e32 v34, 0
	v_mov_b32_e32 v35, 0
	v_mov_b32_e32 v36, 0
	v_mov_b32_e32 v37, 0
	v_mov_b32_e32 v38, 0
	v_mov_b32_e32 v39, 0
	v_mov_b32_e32 v40, 0
	v_mov_b32_e32 v41, 0
	v_mov_b32_e32 v42, 0
	v_mov_b32_e32 v43, 0
	v_mov_b32_e32 v44, 0
	v_mov_b32_e32 v45, 0
	v_mov_b32_e32 v46, 0
	v_mov_b32_e32 v47, 0
	v_mov_b32_e32 v16, 0
	v_mov_b32_e32 v17, 0
	v_mov_b32_e32 v18, 0
	v_mov_b32_e32 v19, 0
	v_mov_b32_e32 v20, 0
	v_mov_b32_e32 v21, 0
	v_mov_b32_e32 v22, 0
	v_mov_b32_e32 v23, 0
	v_mov_b32_e32 v24, 0
	v_mov_b32_e32 v25, 0
	v_mov_b32_e32 v26, 0
	v_mov_b32_e32 v27, 0
	v_mov_b32_e32 v28, 0
	v_mov_b32_e32 v29, 0
	v_mov_b32_e32 v30, 0
	v_mov_b32_e32 v31, 0
	v_mov_b32_e32 v0, 0
	v_mov_b32_e32 v1, 0
	v_mov_b32_e32 v2, 0
	v_mov_b32_e32 v3, 0
	v_mov_b32_e32 v4, 0
	v_mov_b32_e32 v5, 0
	v_mov_b32_e32 v6, 0
	v_mov_b32_e32 v7, 0
	v_mov_b32_e32 v8, 0
	v_mov_b32_e32 v9, 0
	v_mov_b32_e32 v10, 0
	v_mov_b32_e32 v11, 0
	v_mov_b32_e32 v12, 0
	v_mov_b32_e32 v13, 0
	v_mov_b32_e32 v14, 0
	v_mov_b32_e32 v15, 0
	s_mov_b32 s37, 21
.Lgk_loop_p8:
	s_waitcnt vmcnt(8)
	s_barrier
	ds_read_b128 v[70:73], v157
	ds_read_b128 v[74:77], v158 offset:16384
	ds_read_b128 v[78:81], v158 offset:20480
	ds_read_b128 v[82:85], v158 offset:24576
	ds_read_b128 v[86:89], v158 offset:28672
	ds_read_b128 v[90:93], v159
	ds_read_b128 v[94:97], v160 offset:16384
	ds_read_b128 v[98:101], v160 offset:20480
	ds_read_b128 v[102:105], v160 offset:24576
	ds_read_b128 v[106:109], v160 offset:28672
	ds_read_b128 v[110:113], v161
	ds_read_b128 v[202:205], v162 offset:16384
	ds_read_b128 v[206:209], v162 offset:20480
	ds_read_b128 v[210:213], v162 offset:24576
	ds_read_b128 v[214:217], v162 offset:28672
	ds_read_b128 v[218:221], v163
	ds_read_b128 v[222:225], v164 offset:16384
	ds_read_b128 v[226:229], v164 offset:20480
	ds_read_b128 v[230:233], v164 offset:24576
	ds_read_b128 v[234:237], v164 offset:28672
	s_waitcnt lgkmcnt(0)
	s_barrier
	s_mov_b32 m0, s36
	s_setprio 1
	v_mfma_f32_32x32x16_bf16 v[48:63], v[70:73], v[74:77], v[48:63]
	v_mfma_f32_32x32x16_bf16 v[32:47], v[70:73], v[78:81], v[32:47]
	global_load_lds_dwordx4 v254, s[18:19]
	s_add_u32 m0, m0, 0x1000
	v_mfma_f32_32x32x16_bf16 v[16:31], v[70:73], v[82:85], v[16:31]
	v_mfma_f32_32x32x16_bf16 v[0:15], v[70:73], v[86:89], v[0:15]
	global_load_lds_dwordx4 v254, s[20:21]
	s_add_u32 m0, m0, 0x1000
	v_mfma_f32_32x32x16_bf16 v[48:63], v[90:93], v[94:97], v[48:63]
	v_mfma_f32_32x32x16_bf16 v[32:47], v[90:93], v[98:101], v[32:47]
	global_load_lds_dwordx4 v254, s[22:23]
	s_add_u32 m0, m0, 0x1000
	v_mfma_f32_32x32x16_bf16 v[16:31], v[90:93], v[102:105], v[16:31]
	v_mfma_f32_32x32x16_bf16 v[0:15], v[90:93], v[106:109], v[0:15]
	global_load_lds_dwordx4 v254, s[24:25]
	s_add_u32 m0, m0, 0x1000
	v_mfma_f32_32x32x16_bf16 v[48:63], v[110:113], v[202:205], v[48:63]
	v_mfma_f32_32x32x16_bf16 v[32:47], v[110:113], v[206:209], v[32:47]
	global_load_lds_dwordx4 v254, s[26:27]
	s_add_u32 m0, m0, 0x1000
	v_mfma_f32_32x32x16_bf16 v[16:31], v[110:113], v[210:213], v[16:31]
	v_mfma_f32_32x32x16_bf16 v[0:15], v[110:113], v[214:217], v[0:15]
	global_load_lds_dwordx4 v254, s[28:29]
	s_add_u32 m0, m0, 0x1000
	v_mfma_f32_32x32x16_bf16 v[48:63], v[218:221], v[222:225], v[48:63]
	v_mfma_f32_32x32x16_bf16 v[32:47], v[218:221], v[226:229], v[32:47]
	global_load_lds_dwordx4 v254, s[30:31]
	s_add_u32 m0, m0, 0x1000
	v_mfma_f32_32x32x16_bf16 v[16:31], v[218:221], v[230:233], v[16:31]
	v_mfma_f32_32x32x16_bf16 v[0:15], v[218:221], v[234:237], v[0:15]
	global_load_lds_dwordx4 v254, s[34:35]
	s_setprio 0
	v_add_u32_e32 v254, 0x80, v254
	s_waitcnt vmcnt(8)
	s_barrier
	ds_read_b128 v[70:73], v157 offset:32768
	ds_read_b128 v[74:77], v158 offset:49152
	ds_read_b128 v[78:81], v158 offset:53248
	ds_read_b128 v[82:85], v158 offset:57344
	ds_read_b128 v[86:89], v158 offset:61440
	ds_read_b128 v[90:93], v159 offset:32768
	ds_read_b128 v[94:97], v160 offset:49152
	ds_read_b128 v[98:101], v160 offset:53248
	ds_read_b128 v[102:105], v160 offset:57344
	ds_read_b128 v[106:109], v160 offset:61440
	ds_read_b128 v[110:113], v161 offset:32768
	ds_read_b128 v[202:205], v162 offset:49152
	ds_read_b128 v[206:209], v162 offset:53248
	ds_read_b128 v[210:213], v162 offset:57344
	ds_read_b128 v[214:217], v162 offset:61440
	ds_read_b128 v[218:221], v163 offset:32768
	ds_read_b128 v[222:225], v164 offset:49152
	ds_read_b128 v[226:229], v164 offset:53248
	ds_read_b128 v[230:233], v164 offset:57344
	ds_read_b128 v[234:237], v164 offset:61440
	s_waitcnt lgkmcnt(0)
	s_barrier
	s_add_u32 m0, s36, 0x8000
	s_setprio 1
	v_mfma_f32_32x32x16_bf16 v[48:63], v[70:73], v[74:77], v[48:63]
	v_mfma_f32_32x32x16_bf16 v[32:47], v[70:73], v[78:81], v[32:47]
	global_load_lds_dwordx4 v254, s[18:19]
	s_add_u32 m0, m0, 0x1000
	v_mfma_f32_32x32x16_bf16 v[16:31], v[70:73], v[82:85], v[16:31]
	v_mfma_f32_32x32x16_bf16 v[0:15], v[70:73], v[86:89], v[0:15]
	global_load_lds_dwordx4 v254, s[20:21]
	s_add_u32 m0, m0, 0x1000
	v_mfma_f32_32x32x16_bf16 v[48:63], v[90:93], v[94:97], v[48:63]
	v_mfma_f32_32x32x16_bf16 v[32:47], v[90:93], v[98:101], v[32:47]
	global_load_lds_dwordx4 v254, s[22:23]
	s_add_u32 m0, m0, 0x1000
	v_mfma_f32_32x32x16_bf16 v[16:31], v[90:93], v[102:105], v[16:31]
	v_mfma_f32_32x32x16_bf16 v[0:15], v[90:93], v[106:109], v[0:15]
	global_load_lds_dwordx4 v254, s[24:25]
	s_add_u32 m0, m0, 0x1000
	v_mfma_f32_32x32x16_bf16 v[48:63], v[110:113], v[202:205], v[48:63]
	v_mfma_f32_32x32x16_bf16 v[32:47], v[110:113], v[206:209], v[32:47]
	global_load_lds_dwordx4 v254, s[26:27]
	s_add_u32 m0, m0, 0x1000
	v_mfma_f32_32x32x16_bf16 v[16:31], v[110:113], v[210:213], v[16:31]
	v_mfma_f32_32x32x16_bf16 v[0:15], v[110:113], v[214:217], v[0:15]
	global_load_lds_dwordx4 v254, s[28:29]
	s_add_u32 m0, m0, 0x1000
	v_mfma_f32_32x32x16_bf16 v[48:63], v[218:221], v[222:225], v[48:63]
	v_mfma_f32_32x32x16_bf16 v[32:47], v[218:221], v[226:229], v[32:47]
	global_load_lds_dwordx4 v254, s[30:31]
	s_add_u32 m0, m0, 0x1000
	v_mfma_f32_32x32x16_bf16 v[16:31], v[218:221], v[230:233], v[16:31]
	v_mfma_f32_32x32x16_bf16 v[0:15], v[218:221], v[234:237], v[0:15]
	global_load_lds_dwordx4 v254, s[34:35]
	s_setprio 0
	v_add_u32_e32 v254, 0x80, v254
	s_sub_u32 s37, s37, 1
	s_cmp_lg_u32 s37, 0
	s_cbranch_scc1 .Lgk_loop_p8
	s_add_u32 s40, s3, s33
	s_cmp_gt_u32 s40, 0x3ff
	s_cbranch_scc1 .Lgk_tailplain_p8
.LBB0_775_pf_p8:
	s_ashr_i32 s41, s40, 31
	s_lshr_b32 s41, s41, 26
	s_add_i32 s41, s40, s41
	s_ashr_i32 s42, s41, 6
	s_andn2_b32 s41, s41, 63
	s_sub_i32 s41, s40, s41
	s_ashr_i32 s43, s41, 31
	s_lshr_b32 s43, s43, 29
	s_add_i32 s43, s41, s43
	s_ashr_i32 s44, s43, 3
	s_and_b32 s43, s43, -8
	s_lshl_b32 s42, s42, 3
	s_sub_i32 s41, s41, s43
	s_add_i32 s41, s41, s42
	s_lshl_b32 s45, s41, 7
	s_lshl_b32 s46, s44, 7
	s_mul_i32 s38, s41, 0xb0000
	s_add_u32 s18, s14, s38
	s_addc_u32 s19, s15, 0
	s_add_u32 s18, s18, 0x879f000
	s_addc_u32 s19, s19, 0
	s_add_u32 s20, s18, 0x2c000
	s_addc_u32 s21, s19, 0
	s_add_u32 s22, s20, 0x2c000
	s_addc_u32 s23, s21, 0
	s_add_u32 s24, s22, 0x2c000
	s_addc_u32 s25, s23, 0
	s_mul_i32 s38, s44, 0xb0000
	s_add_u32 s26, s14, s38
	s_addc_u32 s27, s15, 0
	s_add_u32 s26, s26, 0x45a0000
	s_addc_u32 s27, s27, 0
	s_add_u32 s28, s26, 0x2c000
	s_addc_u32 s29, s27, 0
	s_add_u32 s30, s28, 0x2c000
	s_addc_u32 s31, s29, 0
	s_add_u32 s34, s30, 0x2c000
	s_addc_u32 s35, s31, 0
	v_mov_b32_e32 v254, v64
	s_mov_b32 s39, 1
	s_waitcnt vmcnt(8)
	s_barrier
	ds_read_b128 v[70:73], v157
	ds_read_b128 v[74:77], v158 offset:16384
	ds_read_b128 v[78:81], v158 offset:20480
	ds_read_b128 v[82:85], v158 offset:24576
	ds_read_b128 v[86:89], v158 offset:28672
	ds_read_b128 v[90:93], v159
	ds_read_b128 v[94:97], v160 offset:16384
	ds_read_b128 v[98:101], v160 offset:20480
	ds_read_b128 v[102:105], v160 offset:24576
	ds_read_b128 v[106:109], v160 offset:28672
	ds_read_b128 v[110:113], v161
	ds_read_b128 v[202:205], v162 offset:16384
	ds_read_b128 v[206:209], v162 offset:20480
	ds_read_b128 v[210:213], v162 offset:24576
	ds_read_b128 v[214:217], v162 offset:28672
	ds_read_b128 v[218:221], v163
	ds_read_b128 v[222:225], v164 offset:16384
	ds_read_b128 v[226:229], v164 offset:20480
	ds_read_b128 v[230:233], v164 offset:24576
	ds_read_b128 v[234:237], v164 offset:28672
	s_waitcnt lgkmcnt(0)
	s_barrier
	s_mov_b32 m0, s36
	s_setprio 1
	v_mfma_f32_32x32x16_bf16 v[48:63], v[70:73], v[74:77], v[48:63]
	v_mfma_f32_32x32x16_bf16 v[32:47], v[70:73], v[78:81], v[32:47]
	global_load_lds_dwordx4 v254, s[18:19]
	s_add_u32 m0, m0, 0x1000
	v_mfma_f32_32x32x16_bf16 v[16:31], v[70:73], v[82:85], v[16:31]
	v_mfma_f32_32x32x16_bf16 v[0:15], v[70:73], v[86:89], v[0:15]
	global_load_lds_dwordx4 v254, s[20:21]
	s_add_u32 m0, m0, 0x1000
	v_mfma_f32_32x32x16_bf16 v[48:63], v[90:93], v[94:97], v[48:63]
	v_mfma_f32_32x32x16_bf16 v[32:47], v[90:93], v[98:101], v[32:47]
	global_load_lds_dwordx4 v254, s[22:23]
	s_add_u32 m0, m0, 0x1000
	v_mfma_f32_32x32x16_bf16 v[16:31], v[90:93], v[102:105], v[16:31]
	v_mfma_f32_32x32x16_bf16 v[0:15], v[90:93], v[106:109], v[0:15]
	global_load_lds_dwordx4 v254, s[24:25]
	s_add_u32 m0, m0, 0x1000
	v_mfma_f32_32x32x16_bf16 v[48:63], v[110:113], v[202:205], v[48:63]
	v_mfma_f32_32x32x16_bf16 v[32:47], v[110:113], v[206:209], v[32:47]
	global_load_lds_dwordx4 v254, s[26:27]
	s_add_u32 m0, m0, 0x1000
	v_mfma_f32_32x32x16_bf16 v[16:31], v[110:113], v[210:213], v[16:31]
	v_mfma_f32_32x32x16_bf16 v[0:15], v[110:113], v[214:217], v[0:15]
	global_load_lds_dwordx4 v254, s[28:29]
	s_add_u32 m0, m0, 0x1000
	v_mfma_f32_32x32x16_bf16 v[48:63], v[218:221], v[222:225], v[48:63]
	v_mfma_f32_32x32x16_bf16 v[32:47], v[218:221], v[226:229], v[32:47]
	global_load_lds_dwordx4 v254, s[30:31]
	s_add_u32 m0, m0, 0x1000
	v_mfma_f32_32x32x16_bf16 v[16:31], v[218:221], v[230:233], v[16:31]
	v_mfma_f32_32x32x16_bf16 v[0:15], v[218:221], v[234:237], v[0:15]
	global_load_lds_dwordx4 v254, s[34:35]
	s_setprio 0
	v_add_u32_e32 v254, 0x80, v254
	s_waitcnt vmcnt(8)
	s_barrier
	ds_read_b128 v[70:73], v157 offset:32768
	ds_read_b128 v[74:77], v158 offset:49152
	ds_read_b128 v[78:81], v158 offset:53248
	ds_read_b128 v[82:85], v158 offset:57344
	ds_read_b128 v[86:89], v158 offset:61440
	ds_read_b128 v[90:93], v159 offset:32768
	ds_read_b128 v[94:97], v160 offset:49152
	ds_read_b128 v[98:101], v160 offset:53248
	ds_read_b128 v[102:105], v160 offset:57344
	ds_read_b128 v[106:109], v160 offset:61440
	ds_read_b128 v[110:113], v161 offset:32768
	ds_read_b128 v[202:205], v162 offset:49152
	ds_read_b128 v[206:209], v162 offset:53248
	ds_read_b128 v[210:213], v162 offset:57344
	ds_read_b128 v[214:217], v162 offset:61440
	ds_read_b128 v[218:221], v163 offset:32768
	ds_read_b128 v[222:225], v164 offset:49152
	ds_read_b128 v[226:229], v164 offset:53248
	ds_read_b128 v[230:233], v164 offset:57344
	ds_read_b128 v[234:237], v164 offset:61440
	s_waitcnt lgkmcnt(0)
	s_barrier
	s_add_u32 m0, s36, 0x8000
	s_setprio 1
	v_mfma_f32_32x32x16_bf16 v[48:63], v[70:73], v[74:77], v[48:63]
	v_mfma_f32_32x32x16_bf16 v[32:47], v[70:73], v[78:81], v[32:47]
	global_load_lds_dwordx4 v254, s[18:19]
	s_add_u32 m0, m0, 0x1000
	v_mfma_f32_32x32x16_bf16 v[16:31], v[70:73], v[82:85], v[16:31]
	v_mfma_f32_32x32x16_bf16 v[0:15], v[70:73], v[86:89], v[0:15]
	global_load_lds_dwordx4 v254, s[20:21]
	s_add_u32 m0, m0, 0x1000
	v_mfma_f32_32x32x16_bf16 v[48:63], v[90:93], v[94:97], v[48:63]
	v_mfma_f32_32x32x16_bf16 v[32:47], v[90:93], v[98:101], v[32:47]
	global_load_lds_dwordx4 v254, s[22:23]
	s_add_u32 m0, m0, 0x1000
	v_mfma_f32_32x32x16_bf16 v[16:31], v[90:93], v[102:105], v[16:31]
	v_mfma_f32_32x32x16_bf16 v[0:15], v[90:93], v[106:109], v[0:15]
	global_load_lds_dwordx4 v254, s[24:25]
	s_add_u32 m0, m0, 0x1000
	v_mfma_f32_32x32x16_bf16 v[48:63], v[110:113], v[202:205], v[48:63]
	v_mfma_f32_32x32x16_bf16 v[32:47], v[110:113], v[206:209], v[32:47]
	global_load_lds_dwordx4 v254, s[26:27]
	s_add_u32 m0, m0, 0x1000
	v_mfma_f32_32x32x16_bf16 v[16:31], v[110:113], v[210:213], v[16:31]
	v_mfma_f32_32x32x16_bf16 v[0:15], v[110:113], v[214:217], v[0:15]
	global_load_lds_dwordx4 v254, s[28:29]
	s_add_u32 m0, m0, 0x1000
	v_mfma_f32_32x32x16_bf16 v[48:63], v[218:221], v[222:225], v[48:63]
	v_mfma_f32_32x32x16_bf16 v[32:47], v[218:221], v[226:229], v[32:47]
	global_load_lds_dwordx4 v254, s[30:31]
	s_add_u32 m0, m0, 0x1000
	v_mfma_f32_32x32x16_bf16 v[16:31], v[218:221], v[230:233], v[16:31]
	v_mfma_f32_32x32x16_bf16 v[0:15], v[218:221], v[234:237], v[0:15]
	global_load_lds_dwordx4 v254, s[34:35]
	s_setprio 0
	v_add_u32_e32 v254, 0x80, v254
	s_branch .LBB0_779
.Lgk_tailplain_p8:
	s_mov_b32 s39, 0
	s_waitcnt vmcnt(8)
	s_barrier
	ds_read_b128 v[70:73], v157
	ds_read_b128 v[74:77], v158 offset:16384
	ds_read_b128 v[78:81], v158 offset:20480
	ds_read_b128 v[82:85], v158 offset:24576
	ds_read_b128 v[86:89], v158 offset:28672
	ds_read_b128 v[90:93], v159
	ds_read_b128 v[94:97], v160 offset:16384
	ds_read_b128 v[98:101], v160 offset:20480
	ds_read_b128 v[102:105], v160 offset:24576
	ds_read_b128 v[106:109], v160 offset:28672
	ds_read_b128 v[110:113], v161
	ds_read_b128 v[202:205], v162 offset:16384
	ds_read_b128 v[206:209], v162 offset:20480
	ds_read_b128 v[210:213], v162 offset:24576
	ds_read_b128 v[214:217], v162 offset:28672
	ds_read_b128 v[218:221], v163
	ds_read_b128 v[222:225], v164 offset:16384
	ds_read_b128 v[226:229], v164 offset:20480
	ds_read_b128 v[230:233], v164 offset:24576
	ds_read_b128 v[234:237], v164 offset:28672
	s_waitcnt lgkmcnt(0)
	s_barrier
	s_setprio 1
	v_mfma_f32_32x32x16_bf16 v[48:63], v[70:73], v[74:77], v[48:63]
	v_mfma_f32_32x32x16_bf16 v[32:47], v[70:73], v[78:81], v[32:47]
	v_mfma_f32_32x32x16_bf16 v[16:31], v[70:73], v[82:85], v[16:31]
	v_mfma_f32_32x32x16_bf16 v[0:15], v[70:73], v[86:89], v[0:15]
	v_mfma_f32_32x32x16_bf16 v[48:63], v[90:93], v[94:97], v[48:63]
	v_mfma_f32_32x32x16_bf16 v[32:47], v[90:93], v[98:101], v[32:47]
	v_mfma_f32_32x32x16_bf16 v[16:31], v[90:93], v[102:105], v[16:31]
	v_mfma_f32_32x32x16_bf16 v[0:15], v[90:93], v[106:109], v[0:15]
	v_mfma_f32_32x32x16_bf16 v[48:63], v[110:113], v[202:205], v[48:63]
	v_mfma_f32_32x32x16_bf16 v[32:47], v[110:113], v[206:209], v[32:47]
	v_mfma_f32_32x32x16_bf16 v[16:31], v[110:113], v[210:213], v[16:31]
	v_mfma_f32_32x32x16_bf16 v[0:15], v[110:113], v[214:217], v[0:15]
	v_mfma_f32_32x32x16_bf16 v[48:63], v[218:221], v[222:225], v[48:63]
	v_mfma_f32_32x32x16_bf16 v[32:47], v[218:221], v[226:229], v[32:47]
	v_mfma_f32_32x32x16_bf16 v[16:31], v[218:221], v[230:233], v[16:31]
	v_mfma_f32_32x32x16_bf16 v[0:15], v[218:221], v[234:237], v[0:15]
	s_setprio 0
	s_waitcnt vmcnt(0)
	s_barrier
	ds_read_b128 v[70:73], v157 offset:32768
	ds_read_b128 v[74:77], v158 offset:49152
	ds_read_b128 v[78:81], v158 offset:53248
	ds_read_b128 v[82:85], v158 offset:57344
	ds_read_b128 v[86:89], v158 offset:61440
	ds_read_b128 v[90:93], v159 offset:32768
	ds_read_b128 v[94:97], v160 offset:49152
	ds_read_b128 v[98:101], v160 offset:53248
	ds_read_b128 v[102:105], v160 offset:57344
	ds_read_b128 v[106:109], v160 offset:61440
	ds_read_b128 v[110:113], v161 offset:32768
	ds_read_b128 v[202:205], v162 offset:49152
	ds_read_b128 v[206:209], v162 offset:53248
	ds_read_b128 v[210:213], v162 offset:57344
	ds_read_b128 v[214:217], v162 offset:61440
	ds_read_b128 v[218:221], v163 offset:32768
	ds_read_b128 v[222:225], v164 offset:49152
	ds_read_b128 v[226:229], v164 offset:53248
	ds_read_b128 v[230:233], v164 offset:57344
	ds_read_b128 v[234:237], v164 offset:61440
	s_waitcnt lgkmcnt(0)
	s_barrier
	s_setprio 1
	v_mfma_f32_32x32x16_bf16 v[48:63], v[70:73], v[74:77], v[48:63]
	v_mfma_f32_32x32x16_bf16 v[32:47], v[70:73], v[78:81], v[32:47]
	v_mfma_f32_32x32x16_bf16 v[16:31], v[70:73], v[82:85], v[16:31]
	v_mfma_f32_32x32x16_bf16 v[0:15], v[70:73], v[86:89], v[0:15]
	v_mfma_f32_32x32x16_bf16 v[48:63], v[90:93], v[94:97], v[48:63]
	v_mfma_f32_32x32x16_bf16 v[32:47], v[90:93], v[98:101], v[32:47]
	v_mfma_f32_32x32x16_bf16 v[16:31], v[90:93], v[102:105], v[16:31]
	v_mfma_f32_32x32x16_bf16 v[0:15], v[90:93], v[106:109], v[0:15]
	v_mfma_f32_32x32x16_bf16 v[48:63], v[110:113], v[202:205], v[48:63]
	v_mfma_f32_32x32x16_bf16 v[32:47], v[110:113], v[206:209], v[32:47]
	v_mfma_f32_32x32x16_bf16 v[16:31], v[110:113], v[210:213], v[16:31]
	v_mfma_f32_32x32x16_bf16 v[0:15], v[110:113], v[214:217], v[0:15]
	v_mfma_f32_32x32x16_bf16 v[48:63], v[218:221], v[222:225], v[48:63]
	v_mfma_f32_32x32x16_bf16 v[32:47], v[218:221], v[226:229], v[32:47]
	v_mfma_f32_32x32x16_bf16 v[16:31], v[218:221], v[230:233], v[16:31]
	v_mfma_f32_32x32x16_bf16 v[0:15], v[218:221], v[234:237], v[0:15]
	s_setprio 0
	s_branch .LBB0_779
.LBB0_779:
	s_add_i32 s58, s67, 0xffffe000
	s_lshr_b32 s58, s58, 12
	s_mulk_i32 s58, 0x1800
	s_addk_i32 s58, 0x1800
	s_cmp_gt_i32 s6, 63
	s_cselect_b32 s6, s58, 0
	s_lshl_b64 s[58:59], s[6:7], 2
	s_add_u32 s58, s14, s58
	s_addc_u32 s59, s15, s59
	s_add_u32 s60, s58, 0x5ba5000
	s_addc_u32 s61, s59, 0
	s_addk_i32 s6, 0x4800
	s_lshl_b64 s[58:59], s[6:7], 2
	v_mov_b32_e32 v70, s66
	s_add_u32 s6, s14, s58
	ds_read_b64 v[70:71], v70
	s_addc_u32 s65, s15, s59
	s_lshl_b32 s58, s64, 14
	s_add_i32 s58, s58, 0x40000
	s_ashr_i32 s59, s58, 31
	s_lshl_b64 s[58:59], s[58:59], 2
	s_add_u32 s58, s10, s58
	s_waitcnt lgkmcnt(0)
	v_readfirstlane_b32 s62, v70
	s_addc_u32 s59, s11, s59
	v_or_b32_e32 v102, s68, v138
	v_add_u32_e32 v70, s67, v139
	v_readfirstlane_b32 s63, v71
	s_add_u32 s62, s62, 0x1000
	v_ashrrev_i32_e32 v103, 31, v102
	v_lshlrev_b32_e32 v191, 10, v70
	s_addc_u32 s63, s63, 0
	v_lshlrev_b64 v[72:73], 2, v[102:103]
	v_or_b32_e32 v187, 0x400, v191
	v_or_b32_e32 v186, 0x4400, v191
	v_or_b32_e32 v189, 0x4c00, v191
	v_or_b32_e32 v194, 0x6c00, v191
	s_add_u32 s64, s6, 0x5ba1000
	v_lshl_add_u64 v[74:75], s[60:61], 0, v[72:73]
	v_add_u32_e32 v130, v191, v102
	v_add_u32_e32 v132, v187, v102
	v_or_b32_e32 v185, 0x800, v191
	v_or_b32_e32 v184, 0xc00, v191
	v_or_b32_e32 v182, 0x2000, v191
	v_or_b32_e32 v180, 0x2400, v191
	v_or_b32_e32 v71, 0x2800, v191
	v_or_b32_e32 v181, 0x2c00, v191
	v_or_b32_e32 v183, 0x4000, v191
	v_add_u32_e32 v112, v186, v102
	v_or_b32_e32 v188, 0x4800, v191
	v_add_u32_e32 v116, v189, v102
	v_or_b32_e32 v190, 0x6000, v191
	v_or_b32_e32 v192, 0x6400, v191
	v_or_b32_e32 v193, 0x6800, v191
	v_add_u32_e32 v128, v194, v102
	s_addc_u32 s65, s65, 0
	global_load_dword v195, v[74:75], off
	v_lshl_add_u64 v[74:75], s[62:63], 0, v[72:73]
	v_ashrrev_i32_e32 v133, 31, v132
	v_add_u32_e32 v134, v185, v102
	v_add_u32_e32 v136, v184, v102
	v_add_u32_e32 v126, v182, v102
	v_add_u32_e32 v118, v180, v102
	v_add_u32_e32 v110, v71, v102
	v_add_u32_e32 v106, v181, v102
	v_add_u32_e32 v108, v183, v102
	v_ashrrev_i32_e32 v113, 31, v112
	v_add_u32_e32 v114, v188, v102
	v_ashrrev_i32_e32 v117, 31, v116
	v_add_u32_e32 v120, v190, v102
	v_add_u32_e32 v122, v192, v102
	v_add_u32_e32 v124, v193, v102
	v_ashrrev_i32_e32 v129, 31, v128
	v_ashrrev_i32_e32 v131, 31, v130
	v_lshl_add_u64 v[72:73], s[64:65], 0, v[72:73]
	global_load_dword v196, v[74:75], off
	global_load_dword v197, v[72:73], off
	v_lshl_add_u64 v[88:89], v[132:133], 2, s[12:13]
	v_ashrrev_i32_e32 v135, 31, v134
	v_ashrrev_i32_e32 v137, 31, v136
	v_ashrrev_i32_e32 v127, 31, v126
	v_ashrrev_i32_e32 v119, 31, v118
	v_ashrrev_i32_e32 v111, 31, v110
	v_ashrrev_i32_e32 v107, 31, v106
	v_ashrrev_i32_e32 v109, 31, v108
	v_lshl_add_u64 v[86:87], v[112:113], 2, s[12:13]
	v_ashrrev_i32_e32 v115, 31, v114
	v_lshl_add_u64 v[92:93], v[116:117], 2, s[12:13]
	v_ashrrev_i32_e32 v121, 31, v120
	v_ashrrev_i32_e32 v123, 31, v122
	v_ashrrev_i32_e32 v125, 31, v124
	v_lshl_add_u64 v[100:101], v[128:129], 2, s[12:13]
	v_lshl_add_u64 v[104:105], v[130:131], 2, s[12:13]
	v_lshl_add_u64 v[84:85], v[134:135], 2, s[12:13]
	v_lshl_add_u64 v[82:83], v[136:137], 2, s[12:13]
	v_lshl_add_u64 v[78:79], v[126:127], 2, s[12:13]
	v_lshl_add_u64 v[72:73], v[118:119], 2, s[12:13]
	v_lshl_add_u64 v[74:75], v[110:111], 2, s[12:13]
	v_lshl_add_u64 v[76:77], v[106:107], 2, s[12:13]
	v_lshl_add_u64 v[80:81], v[108:109], 2, s[12:13]
	global_load_dword v179, v[88:89], off
	global_load_dword v178, v[84:85], off
	global_load_dword v177, v[82:83], off
	global_load_dword v176, v[78:79], off
	global_load_dword v175, v[72:73], off
	global_load_dword v174, v[74:75], off
	global_load_dword v173, v[76:77], off
	global_load_dword v172, v[80:81], off
	v_lshl_add_u64 v[90:91], v[114:115], 2, s[12:13]
	global_load_dword v171, v[86:87], off
	global_load_dword v169, v[90:91], off
	v_lshl_add_u64 v[94:95], v[120:121], 2, s[12:13]
	v_lshl_add_u64 v[96:97], v[122:123], 2, s[12:13]
	v_lshl_add_u64 v[98:99], v[124:125], 2, s[12:13]
	global_load_dword v170, v[92:93], off
	global_load_dword v168, v[94:95], off
	global_load_dword v167, v[96:97], off
	global_load_dword v166, v[98:99], off
	global_load_dword v103, v[100:101], off
	global_load_dword v198, v[104:105], off
	v_lshl_add_u64 v[110:111], v[110:111], 1, s[8:9]
	v_lshl_add_u64 v[106:107], v[106:107], 1, s[8:9]
	s_waitcnt vmcnt(0)
	v_add_f32_e32 v197, 1.0, v197
	v_mul_f32_e32 v196, v196, v197
	v_fmac_f32_e32 v179, v49, v195
	v_fmac_f32_e32 v178, v50, v195
	v_fmac_f32_e32 v177, v51, v195
	v_fmac_f32_e32 v176, v52, v195
	v_fmac_f32_e32 v175, v53, v195
	v_fmac_f32_e32 v174, v54, v195
	v_fmac_f32_e32 v173, v55, v195
	v_fmac_f32_e32 v172, v56, v195
	v_fmac_f32_e32 v171, v57, v195
	v_fmac_f32_e32 v169, v58, v195
	v_fmac_f32_e32 v170, v59, v195
	v_fmac_f32_e32 v168, v60, v195
	v_fmac_f32_e32 v167, v61, v195
	v_fmac_f32_e32 v166, v62, v195
	v_fmac_f32_e32 v103, v63, v195
	v_fmac_f32_e32 v198, v48, v195
	v_mul_f32_e32 v48, v196, v198
	v_cvt_pk_bf16_f32 v58, v48, s0
	v_or_b32_e32 v48, 32, v102
	v_ashrrev_i32_e32 v49, 31, v48
	v_lshlrev_b64 v[52:53], 2, v[48:49]
	global_store_dword v[88:89], v179, off sc1
	global_store_dword v[84:85], v178, off sc1
	global_store_dword v[82:83], v177, off sc1
	global_store_dword v[78:79], v176, off sc1
	global_store_dword v[72:73], v175, off sc1
	global_store_dword v[74:75], v174, off sc1
	global_store_dword v[76:77], v173, off sc1
	global_store_dword v[80:81], v172, off sc1
	global_store_dword v[86:87], v171, off sc1
	global_store_dword v[90:91], v169, off sc1
	global_store_dword v[92:93], v170, off sc1
	global_store_dword v[94:95], v168, off sc1
	global_store_dword v[96:97], v167, off sc1
	global_store_dword v[98:99], v166, off sc1
	global_store_dword v[100:101], v103, off sc1
	global_store_dword v[104:105], v198, off sc1
	v_lshl_add_u64 v[50:51], v[130:131], 1, s[8:9]
	v_lshl_add_u64 v[56:57], s[64:65], 0, v[52:53]
	global_load_dword v197, v[104:105], off offset:128
	v_lshl_add_u64 v[54:55], s[62:63], 0, v[52:53]
	global_load_dword v130, v[56:57], off
	global_load_dword v131, v[54:55], off
	v_mul_f32_e32 v49, v196, v179
	global_store_short v[50:51], v58, off sc1
	v_lshl_add_u64 v[50:51], s[60:61], 0, v[52:53]
	global_load_dword v195, v[50:51], off
	v_lshl_add_u64 v[50:51], v[132:133], 1, s[8:9]
	v_cvt_pk_bf16_f32 v49, v49, s0
	global_store_short v[50:51], v49, off sc1
	v_mul_f32_e32 v49, v196, v178
	v_lshl_add_u64 v[50:51], v[134:135], 1, s[8:9]
	v_cvt_pk_bf16_f32 v49, v49, s0
	global_store_short v[50:51], v49, off sc1
	v_mul_f32_e32 v49, v196, v177
	v_lshl_add_u64 v[50:51], v[136:137], 1, s[8:9]
	v_cvt_pk_bf16_f32 v49, v49, s0
	global_store_short v[50:51], v49, off sc1
	v_mul_f32_e32 v49, v196, v176
	v_lshl_add_u64 v[50:51], v[126:127], 1, s[8:9]
	v_cvt_pk_bf16_f32 v49, v49, s0
	global_store_short v[50:51], v49, off sc1
	v_mul_f32_e32 v49, v196, v175
	v_lshl_add_u64 v[50:51], v[118:119], 1, s[8:9]
	v_cvt_pk_bf16_f32 v49, v49, s0
	global_load_dword v62, v[84:85], off offset:128
	global_load_dword v60, v[78:79], off offset:128
	global_load_dword v59, v[72:73], off offset:128
	global_load_dword v58, v[74:75], off offset:128
	global_load_dword v56, v[80:81], off offset:128
	global_load_dword v57, v[76:77], off offset:128
	global_load_dword v55, v[86:87], off offset:128
	global_load_dword v61, v[82:83], off offset:128
	global_load_dword v54, v[90:91], off offset:128
	global_load_dword v53, v[92:93], off offset:128
	global_load_dword v52, v[94:95], off offset:128
	v_mul_f32_e32 v63, v196, v174
	global_store_short v[50:51], v49, off sc1
	global_load_dword v51, v[96:97], off offset:128
	v_cvt_pk_bf16_f32 v63, v63, s0
	global_load_dword v50, v[98:99], off offset:128
	global_load_dword v49, v[100:101], off offset:128
	s_waitcnt vmcnt(19)
	v_fmac_f32_e32 v197, v32, v195
	global_store_short v[110:111], v63, off sc1
	global_load_dword v63, v[88:89], off offset:128
	v_mul_f32_e32 v110, v196, v173
	v_cvt_pk_bf16_f32 v110, v110, s0
	global_store_short v[106:107], v110, off sc1
	v_lshl_add_u64 v[106:107], v[108:109], 1, s[8:9]
	v_mul_f32_e32 v108, v196, v172
	v_cvt_pk_bf16_f32 v108, v108, s0
	global_store_short v[106:107], v108, off sc1
	v_mul_f32_e32 v108, v196, v171
	v_lshl_add_u64 v[106:107], v[112:113], 1, s[8:9]
	v_cvt_pk_bf16_f32 v108, v108, s0
	global_store_short v[106:107], v108, off sc1
	v_mul_f32_e32 v108, v196, v169
	v_lshl_add_u64 v[106:107], v[114:115], 1, s[8:9]
	v_cvt_pk_bf16_f32 v108, v108, s0
	global_store_short v[106:107], v108, off sc1
	v_mul_f32_e32 v108, v196, v170
	v_lshl_add_u64 v[106:107], v[116:117], 1, s[8:9]
	v_cvt_pk_bf16_f32 v108, v108, s0
	global_store_short v[106:107], v108, off sc1
	v_mul_f32_e32 v108, v196, v168
	v_lshl_add_u64 v[106:107], v[120:121], 1, s[8:9]
	v_cvt_pk_bf16_f32 v108, v108, s0
	global_store_short v[106:107], v108, off sc1
	v_mul_f32_e32 v108, v196, v167
	v_lshl_add_u64 v[106:107], v[122:123], 1, s[8:9]
	v_cvt_pk_bf16_f32 v108, v108, s0
	global_store_short v[106:107], v108, off sc1
	v_mul_f32_e32 v108, v196, v166
	v_lshl_add_u64 v[106:107], v[124:125], 1, s[8:9]
	v_cvt_pk_bf16_f32 v108, v108, s0
	global_store_short v[106:107], v108, off sc1
	v_mul_f32_e32 v108, v196, v103
	v_lshl_add_u64 v[106:107], v[128:129], 1, s[8:9]
	v_cvt_pk_bf16_f32 v108, v108, s0
	global_store_short v[106:107], v108, off sc1
	v_add_f32_e32 v106, 1.0, v130
	v_mul_f32_e32 v107, v131, v106
	v_add_u32_e32 v108, v191, v48
	v_ashrrev_i32_e32 v109, 31, v108
	v_mul_f32_e32 v32, v107, v197
	s_waitcnt vmcnt(25)
	v_fmac_f32_e32 v62, v34, v195
	s_waitcnt vmcnt(18)
	v_fmac_f32_e32 v61, v35, v195
	v_fmac_f32_e32 v60, v36, v195
	v_fmac_f32_e32 v59, v37, v195
	v_fmac_f32_e32 v58, v38, v195
	v_fmac_f32_e32 v57, v39, v195
	v_fmac_f32_e32 v56, v40, v195
	v_fmac_f32_e32 v55, v41, v195
	s_waitcnt vmcnt(17)
	v_fmac_f32_e32 v54, v42, v195
	s_waitcnt vmcnt(16)
	v_fmac_f32_e32 v53, v43, v195
	s_waitcnt vmcnt(15)
	v_fmac_f32_e32 v52, v44, v195
	s_waitcnt vmcnt(13)
	v_fmac_f32_e32 v51, v45, v195
	s_waitcnt vmcnt(12)
	v_fmac_f32_e32 v50, v46, v195
	s_waitcnt vmcnt(11)
	v_fmac_f32_e32 v49, v47, v195
	global_store_dword v[104:105], v197, off offset:128 sc1
	v_lshl_add_u64 v[108:109], v[108:109], 1, s[8:9]
	v_cvt_pk_bf16_f32 v32, v32, s0
	global_store_dword v[84:85], v62, off offset:128 sc1
	global_store_dword v[82:83], v61, off offset:128 sc1
	global_store_dword v[78:79], v60, off offset:128 sc1
	global_store_dword v[72:73], v59, off offset:128 sc1
	global_store_dword v[74:75], v58, off offset:128 sc1
	global_store_dword v[76:77], v57, off offset:128 sc1
	global_store_dword v[80:81], v56, off offset:128 sc1
	global_store_dword v[86:87], v55, off offset:128 sc1
	global_store_dword v[90:91], v54, off offset:128 sc1
	global_store_dword v[92:93], v53, off offset:128 sc1
	global_store_dword v[94:95], v52, off offset:128 sc1
	global_store_dword v[96:97], v51, off offset:128 sc1
	global_store_dword v[98:99], v50, off offset:128 sc1
	global_store_dword v[100:101], v49, off offset:128 sc1
	global_store_short v[108:109], v32, off sc1
	v_add_u32_e32 v108, v187, v48
	global_load_dword v45, v[88:89], off offset:256
	v_ashrrev_i32_e32 v109, 31, v108
	v_mul_f32_e32 v113, v107, v56
	v_cvt_pk_bf16_f32 v113, v113, s0
	v_mul_f32_e32 v106, v197, v197
	v_fmac_f32_e32 v106, v198, v198
	s_waitcnt vmcnt(26)
	v_fmac_f32_e32 v63, v33, v195
	v_mul_f32_e32 v34, v107, v63
	v_lshl_add_u64 v[32:33], v[108:109], 1, s[8:9]
	v_cvt_pk_bf16_f32 v34, v34, s0
	global_store_short v[32:33], v34, off sc1
	v_add_u32_e32 v32, v185, v48
	v_ashrrev_i32_e32 v33, 31, v32
	v_mul_f32_e32 v34, v107, v62
	v_lshl_add_u64 v[32:33], v[32:33], 1, s[8:9]
	v_cvt_pk_bf16_f32 v34, v34, s0
	global_store_short v[32:33], v34, off sc1
	v_add_u32_e32 v32, v184, v48
	v_ashrrev_i32_e32 v33, 31, v32
	v_mul_f32_e32 v34, v107, v61
	v_lshl_add_u64 v[32:33], v[32:33], 1, s[8:9]
	v_cvt_pk_bf16_f32 v34, v34, s0
	global_store_short v[32:33], v34, off sc1
	v_add_u32_e32 v32, v182, v48
	v_ashrrev_i32_e32 v33, 31, v32
	v_mul_f32_e32 v34, v107, v60
	v_lshl_add_u64 v[32:33], v[32:33], 1, s[8:9]
	v_cvt_pk_bf16_f32 v34, v34, s0
	global_store_short v[32:33], v34, off sc1
	v_add_u32_e32 v32, v180, v48
	v_ashrrev_i32_e32 v33, 31, v32
	v_lshl_add_u64 v[34:35], v[32:33], 1, s[8:9]
	v_mul_f32_e32 v32, v107, v59
	v_cvt_pk_bf16_f32 v42, v32, s0
	v_or_b32_e32 v32, 64, v102
	v_ashrrev_i32_e32 v33, 31, v32
	v_lshlrev_b64 v[36:37], 2, v[32:33]
	global_store_dword v[88:89], v63, off offset:128 sc1
	v_lshl_add_u64 v[40:41], s[64:65], 0, v[36:37]
	v_lshl_add_u64 v[38:39], s[62:63], 0, v[36:37]
	global_load_dword v110, v[40:41], off
	global_load_dword v111, v[38:39], off
	v_mul_f32_e32 v33, v107, v58
	global_store_short v[34:35], v42, off sc1
	v_lshl_add_u64 v[34:35], s[60:61], 0, v[36:37]
	global_load_dword v112, v[34:35], off
	v_add_u32_e32 v34, v71, v48
	v_ashrrev_i32_e32 v35, 31, v34
	v_lshl_add_u64 v[34:35], v[34:35], 1, s[8:9]
	v_cvt_pk_bf16_f32 v33, v33, s0
	global_store_short v[34:35], v33, off sc1
	v_add_u32_e32 v34, v181, v48
	v_ashrrev_i32_e32 v35, 31, v34
	v_mul_f32_e32 v33, v107, v57
	v_lshl_add_u64 v[34:35], v[34:35], 1, s[8:9]
	v_cvt_pk_bf16_f32 v33, v33, s0
	global_load_dword v38, v[90:91], off offset:256
	global_load_dword v37, v[92:93], off offset:256
	global_load_dword v36, v[94:95], off offset:256
	global_load_dword v114, v[104:105], off offset:256
	global_load_dword v47, v[84:85], off offset:256
	global_load_dword v39, v[86:87], off offset:256
	global_load_dword v46, v[82:83], off offset:256
	global_load_dword v44, v[78:79], off offset:256
	global_load_dword v43, v[72:73], off offset:256
	global_load_dword v42, v[74:75], off offset:256
	global_load_dword v40, v[80:81], off offset:256
	global_load_dword v41, v[76:77], off offset:256
	v_add_u32_e32 v108, v183, v48
	global_store_short v[34:35], v33, off sc1
	global_load_dword v35, v[96:97], off offset:256
	v_ashrrev_i32_e32 v109, 31, v108
	global_load_dword v34, v[98:99], off offset:256
	global_load_dword v33, v[100:101], off offset:256
	v_lshl_add_u64 v[108:109], v[108:109], 1, s[8:9]
	global_store_short v[108:109], v113, off sc1
	v_add_u32_e32 v108, v186, v48
	v_ashrrev_i32_e32 v109, 31, v108
	v_mul_f32_e32 v113, v107, v55
	v_lshl_add_u64 v[108:109], v[108:109], 1, s[8:9]
	v_cvt_pk_bf16_f32 v113, v113, s0
	global_store_short v[108:109], v113, off sc1
	v_add_u32_e32 v108, v188, v48
	v_ashrrev_i32_e32 v109, 31, v108
	v_mul_f32_e32 v113, v107, v54
	v_lshl_add_u64 v[108:109], v[108:109], 1, s[8:9]
	v_cvt_pk_bf16_f32 v113, v113, s0
	global_store_short v[108:109], v113, off sc1
	v_add_u32_e32 v108, v189, v48
	v_ashrrev_i32_e32 v109, 31, v108
	v_mul_f32_e32 v113, v107, v53
	v_lshl_add_u64 v[108:109], v[108:109], 1, s[8:9]
	v_cvt_pk_bf16_f32 v113, v113, s0
	global_store_short v[108:109], v113, off sc1
	v_add_u32_e32 v108, v190, v48
	v_ashrrev_i32_e32 v109, 31, v108
	v_mul_f32_e32 v113, v107, v52
	v_lshl_add_u64 v[108:109], v[108:109], 1, s[8:9]
	v_cvt_pk_bf16_f32 v113, v113, s0
	global_store_short v[108:109], v113, off sc1
	v_add_u32_e32 v108, v192, v48
	v_ashrrev_i32_e32 v109, 31, v108
	v_mul_f32_e32 v113, v107, v51
	v_lshl_add_u64 v[108:109], v[108:109], 1, s[8:9]
	v_cvt_pk_bf16_f32 v113, v113, s0
	global_store_short v[108:109], v113, off sc1
	v_add_u32_e32 v108, v193, v48
	v_ashrrev_i32_e32 v109, 31, v108
	v_mul_f32_e32 v113, v107, v50
	v_lshl_add_u64 v[108:109], v[108:109], 1, s[8:9]
	v_cvt_pk_bf16_f32 v113, v113, s0
	global_store_short v[108:109], v113, off sc1
	v_add_u32_e32 v108, v194, v48
	v_ashrrev_i32_e32 v109, 31, v108
	v_mul_f32_e32 v48, v107, v49
	v_lshl_add_u64 v[108:109], v[108:109], 1, s[8:9]
	v_cvt_pk_bf16_f32 v48, v48, s0
	global_store_short v[108:109], v48, off sc1
	v_add_u32_e32 v108, v191, v32
	v_ashrrev_i32_e32 v109, 31, v108
	s_waitcnt vmcnt(28)
	v_add_f32_e32 v48, 1.0, v110
	s_waitcnt vmcnt(27)
	v_mul_f32_e32 v48, v111, v48
	s_waitcnt vmcnt(25)
	v_fmac_f32_e32 v45, v17, v112
	global_store_dword v[88:89], v45, off offset:256 sc1
	s_waitcnt vmcnt(24)
	v_fmac_f32_e32 v38, v26, v112
	s_waitcnt vmcnt(23)
	v_fmac_f32_e32 v37, v27, v112
	s_waitcnt vmcnt(22)
	v_fmac_f32_e32 v36, v28, v112
	s_waitcnt vmcnt(21)
	v_fmac_f32_e32 v114, v16, v112
	s_waitcnt vmcnt(20)
	v_fmac_f32_e32 v47, v18, v112
	v_mul_f32_e32 v18, v48, v114
	v_lshl_add_u64 v[16:17], v[108:109], 1, s[8:9]
	v_cvt_pk_bf16_f32 v18, v18, s0
	global_store_short v[16:17], v18, off sc1
	v_add_u32_e32 v16, v187, v32
	v_ashrrev_i32_e32 v17, 31, v16
	v_mul_f32_e32 v18, v48, v45
	v_lshl_add_u64 v[16:17], v[16:17], 1, s[8:9]
	v_cvt_pk_bf16_f32 v18, v18, s0
	global_store_short v[16:17], v18, off sc1
	v_add_u32_e32 v16, v185, v32
	v_ashrrev_i32_e32 v17, 31, v16
	v_mul_f32_e32 v18, v48, v47
	v_lshl_add_u64 v[16:17], v[16:17], 1, s[8:9]
	v_cvt_pk_bf16_f32 v18, v18, s0
	s_waitcnt vmcnt(20)
	v_fmac_f32_e32 v46, v19, v112
	global_store_short v[16:17], v18, off sc1
	v_add_u32_e32 v16, v184, v32
	v_ashrrev_i32_e32 v17, 31, v16
	v_mul_f32_e32 v18, v48, v46
	v_lshl_add_u64 v[16:17], v[16:17], 1, s[8:9]
	v_cvt_pk_bf16_f32 v18, v18, s0
	global_store_short v[16:17], v18, off sc1
	v_add_u32_e32 v16, v182, v32
	v_ashrrev_i32_e32 v17, 31, v16
	v_lshl_add_u64 v[18:19], v[16:17], 1, s[8:9]
	v_or_b32_e32 v16, 0x60, v102
	v_ashrrev_i32_e32 v17, 31, v16
	s_waitcnt vmcnt(21)
	v_fmac_f32_e32 v44, v20, v112
	s_waitcnt vmcnt(20)
	v_fmac_f32_e32 v43, v21, v112
	s_waitcnt vmcnt(19)
	v_fmac_f32_e32 v42, v22, v112
	s_waitcnt vmcnt(17)
	v_fmac_f32_e32 v41, v23, v112
	v_fmac_f32_e32 v40, v24, v112
	v_fmac_f32_e32 v39, v25, v112
	s_waitcnt vmcnt(15)
	v_fmac_f32_e32 v35, v29, v112
	s_waitcnt vmcnt(14)
	v_fmac_f32_e32 v34, v30, v112
	s_waitcnt vmcnt(13)
	v_fmac_f32_e32 v33, v31, v112
	v_lshlrev_b64 v[20:21], 2, v[16:17]
	global_store_dword v[84:85], v47, off offset:256 sc1
	global_store_dword v[82:83], v46, off offset:256 sc1
	global_store_dword v[78:79], v44, off offset:256 sc1
	global_store_dword v[72:73], v43, off offset:256 sc1
	global_store_dword v[74:75], v42, off offset:256 sc1
	global_store_dword v[76:77], v41, off offset:256 sc1
	global_store_dword v[80:81], v40, off offset:256 sc1
	global_store_dword v[86:87], v39, off offset:256 sc1
	global_store_dword v[90:91], v38, off offset:256 sc1
	global_store_dword v[92:93], v37, off offset:256 sc1
	global_store_dword v[94:95], v36, off offset:256 sc1
	global_store_dword v[96:97], v35, off offset:256 sc1
	global_store_dword v[98:99], v34, off offset:256 sc1
	global_store_dword v[100:101], v33, off offset:256 sc1
	global_store_dword v[104:105], v114, off offset:256 sc1
	v_mul_f32_e32 v26, v48, v44
	v_lshl_add_u64 v[22:23], s[62:63], 0, v[20:21]
	v_lshl_add_u64 v[24:25], s[64:65], 0, v[20:21]
	global_load_dword v29, v[104:105], off offset:384
	global_load_dword v17, v[24:25], off
	global_load_dword v30, v[22:23], off
	v_cvt_pk_bf16_f32 v22, v26, s0
	global_store_short v[18:19], v22, off sc1
	v_lshl_add_u64 v[18:19], s[60:61], 0, v[20:21]
	global_load_dword v102, v[18:19], off
	v_add_u32_e32 v18, v180, v32
	v_ashrrev_i32_e32 v19, 31, v18
	v_mul_f32_e32 v20, v48, v43
	v_lshl_add_u64 v[18:19], v[18:19], 1, s[8:9]
	v_cvt_pk_bf16_f32 v20, v20, s0
	global_store_short v[18:19], v20, off sc1
	v_add_u32_e32 v18, v71, v32
	v_ashrrev_i32_e32 v19, 31, v18
	v_mul_f32_e32 v20, v48, v42
	v_lshl_add_u64 v[18:19], v[18:19], 1, s[8:9]
	v_cvt_pk_bf16_f32 v20, v20, s0
	global_store_short v[18:19], v20, off sc1
	v_add_u32_e32 v18, v181, v32
	v_ashrrev_i32_e32 v19, 31, v18
	v_mul_f32_e32 v20, v48, v41
	v_lshl_add_u64 v[18:19], v[18:19], 1, s[8:9]
	v_cvt_pk_bf16_f32 v20, v20, s0
	global_store_short v[18:19], v20, off sc1
	v_add_u32_e32 v18, v183, v32
	v_ashrrev_i32_e32 v19, 31, v18
	v_mul_f32_e32 v20, v48, v40
	v_lshl_add_u64 v[18:19], v[18:19], 1, s[8:9]
	v_cvt_pk_bf16_f32 v20, v20, s0
	global_store_short v[18:19], v20, off sc1
	v_add_u32_e32 v18, v186, v32
	v_ashrrev_i32_e32 v19, 31, v18
	v_mul_f32_e32 v20, v48, v39
	v_lshl_add_u64 v[18:19], v[18:19], 1, s[8:9]
	v_cvt_pk_bf16_f32 v20, v20, s0
	global_store_short v[18:19], v20, off sc1
	v_add_u32_e32 v18, v188, v32
	v_ashrrev_i32_e32 v19, 31, v18
	v_mul_f32_e32 v20, v48, v38
	v_lshl_add_u64 v[18:19], v[18:19], 1, s[8:9]
	v_cvt_pk_bf16_f32 v20, v20, s0
	global_store_short v[18:19], v20, off sc1
	v_add_u32_e32 v18, v189, v32
	v_ashrrev_i32_e32 v19, 31, v18
	v_mul_f32_e32 v20, v48, v37
	v_lshl_add_u64 v[18:19], v[18:19], 1, s[8:9]
	v_cvt_pk_bf16_f32 v20, v20, s0
	global_store_short v[18:19], v20, off sc1
	v_add_u32_e32 v18, v190, v32
	v_ashrrev_i32_e32 v19, 31, v18
	v_mul_f32_e32 v20, v48, v36
	v_lshl_add_u64 v[18:19], v[18:19], 1, s[8:9]
	v_cvt_pk_bf16_f32 v20, v20, s0
	global_store_short v[18:19], v20, off sc1
	v_add_u32_e32 v18, v192, v32
	v_ashrrev_i32_e32 v19, 31, v18
	v_mul_f32_e32 v20, v48, v35
	v_lshl_add_u64 v[18:19], v[18:19], 1, s[8:9]
	v_cvt_pk_bf16_f32 v20, v20, s0
	global_load_dword v28, v[88:89], off offset:384
	global_load_dword v27, v[84:85], off offset:384
	global_load_dword v25, v[78:79], off offset:384
	global_load_dword v24, v[72:73], off offset:384
	global_load_dword v23, v[74:75], off offset:384
	global_load_dword v21, v[80:81], off offset:384
	global_load_dword v22, v[76:77], off offset:384
	v_fmac_f32_e32 v106, v114, v114
	global_store_short v[18:19], v20, off sc1
	v_add_u32_e32 v18, v193, v32
	v_ashrrev_i32_e32 v19, 31, v18
	v_mul_f32_e32 v20, v48, v34
	v_lshl_add_u64 v[18:19], v[18:19], 1, s[8:9]
	v_cvt_pk_bf16_f32 v20, v20, s0
	global_store_short v[18:19], v20, off sc1
	v_add_u32_e32 v18, v194, v32
	v_ashrrev_i32_e32 v19, 31, v18
	v_mul_f32_e32 v20, v48, v33
	v_lshl_add_u64 v[18:19], v[18:19], 1, s[8:9]
	v_cvt_pk_bf16_f32 v20, v20, s0
	global_store_short v[18:19], v20, off sc1
	global_load_dword v20, v[86:87], off offset:384
	s_waitcnt vmcnt(22)
	v_add_f32_e32 v17, 1.0, v17
	global_load_dword v26, v[82:83], off offset:384
	s_waitcnt vmcnt(22)
	v_mul_f32_e32 v32, v30, v17
	v_add_u32_e32 v18, v191, v16
	s_waitcnt vmcnt(20)
	v_fmac_f32_e32 v29, v0, v102
	v_ashrrev_i32_e32 v19, 31, v18
	v_mul_f32_e32 v0, v32, v29
	v_lshl_add_u64 v[18:19], v[18:19], 1, s[8:9]
	v_cvt_pk_bf16_f32 v0, v0, s0
	global_store_short v[18:19], v0, off sc1
	global_load_dword v19, v[90:91], off offset:384
	v_add_u32_e32 v30, v187, v16
	global_load_dword v18, v[92:93], off offset:384
	v_ashrrev_i32_e32 v31, 31, v30
	v_fmac_f32_e32 v106, v29, v29
	global_store_dword v[104:105], v29, off offset:384 sc1
	s_waitcnt vmcnt(15)
	v_fmac_f32_e32 v28, v1, v102
	v_mul_f32_e32 v17, v32, v28
	v_lshl_add_u64 v[0:1], v[30:31], 1, s[8:9]
	v_cvt_pk_bf16_f32 v17, v17, s0
	global_store_short v[0:1], v17, off sc1
	v_add_u32_e32 v0, v185, v16
	s_waitcnt vmcnt(15)
	v_fmac_f32_e32 v27, v2, v102
	global_load_dword v17, v[94:95], off offset:384
	v_ashrrev_i32_e32 v1, 31, v0
	v_mul_f32_e32 v2, v32, v27
	v_lshl_add_u64 v[0:1], v[0:1], 1, s[8:9]
	v_cvt_pk_bf16_f32 v2, v2, s0
	global_store_short v[0:1], v2, off sc1
	v_add_u32_e32 v0, v184, v16
	global_load_dword v2, v[96:97], off offset:384
	v_ashrrev_i32_e32 v1, 31, v0
	v_lshl_add_u64 v[0:1], v[0:1], 1, s[8:9]
	v_add_u32_e32 v30, v182, v16
	s_waitcnt vmcnt(17)
	v_fmac_f32_e32 v25, v4, v102
	v_ashrrev_i32_e32 v31, 31, v30
	v_lshl_add_u64 v[30:31], v[30:31], 1, s[8:9]
	s_waitcnt vmcnt(16)
	v_fmac_f32_e32 v24, v5, v102
	s_waitcnt vmcnt(15)
	v_fmac_f32_e32 v23, v6, v102
	s_waitcnt vmcnt(8)
	v_fmac_f32_e32 v26, v3, v102
	v_mul_f32_e32 v3, v32, v26
	v_cvt_pk_bf16_f32 v3, v3, s0
	global_store_short v[0:1], v3, off sc1
	global_load_dword v1, v[98:99], off offset:384
	v_mul_f32_e32 v0, v32, v25
	v_cvt_pk_bf16_f32 v0, v0, s0
	global_store_short v[30:31], v0, off sc1
	global_load_dword v0, v[100:101], off offset:384
	v_add_u32_e32 v30, v180, v16
	v_ashrrev_i32_e32 v31, 31, v30
	v_mul_f32_e32 v3, v32, v24
	v_lshl_add_u64 v[4:5], v[30:31], 1, s[8:9]
	v_cvt_pk_bf16_f32 v3, v3, s0
	global_store_short v[4:5], v3, off sc1
	v_add_u32_e32 v4, v71, v16
	v_ashrrev_i32_e32 v5, 31, v4
	v_mul_f32_e32 v3, v32, v23
	v_lshl_add_u64 v[4:5], v[4:5], 1, s[8:9]
	v_cvt_pk_bf16_f32 v3, v3, s0
	global_store_short v[4:5], v3, off sc1
	v_add_u32_e32 v4, v181, v16
	v_fmac_f32_e32 v22, v7, v102
	v_ashrrev_i32_e32 v5, 31, v4
	v_mul_f32_e32 v3, v32, v22
	v_lshl_add_u64 v[4:5], v[4:5], 1, s[8:9]
	v_cvt_pk_bf16_f32 v3, v3, s0
	global_store_short v[4:5], v3, off sc1
	v_add_u32_e32 v4, v183, v16
	v_fmac_f32_e32 v21, v8, v102
	v_ashrrev_i32_e32 v5, 31, v4
	v_mul_f32_e32 v3, v32, v21
	v_lshl_add_u64 v[4:5], v[4:5], 1, s[8:9]
	v_cvt_pk_bf16_f32 v3, v3, s0
	global_store_short v[4:5], v3, off sc1
	v_add_u32_e32 v4, v186, v16
	v_fmac_f32_e32 v20, v9, v102
	v_ashrrev_i32_e32 v5, 31, v4
	v_mul_f32_e32 v3, v32, v20
	v_lshl_add_u64 v[4:5], v[4:5], 1, s[8:9]
	v_cvt_pk_bf16_f32 v3, v3, s0
	global_store_short v[4:5], v3, off sc1
	v_add_u32_e32 v4, v188, v16
	s_waitcnt vmcnt(15)
	v_fmac_f32_e32 v19, v10, v102
	v_ashrrev_i32_e32 v5, 31, v4
	v_mul_f32_e32 v3, v32, v19
	v_lshl_add_u64 v[4:5], v[4:5], 1, s[8:9]
	v_cvt_pk_bf16_f32 v3, v3, s0
	global_store_short v[4:5], v3, off sc1
	v_add_u32_e32 v4, v189, v16
	s_waitcnt vmcnt(15)
	v_fmac_f32_e32 v18, v11, v102
	v_ashrrev_i32_e32 v5, 31, v4
	v_mul_f32_e32 v3, v32, v18
	v_lshl_add_u64 v[4:5], v[4:5], 1, s[8:9]
	v_cvt_pk_bf16_f32 v3, v3, s0
	global_store_short v[4:5], v3, off sc1
	v_add_u32_e32 v4, v190, v16
	v_ashrrev_i32_e32 v5, 31, v4
	v_lshl_add_u64 v[4:5], v[4:5], 1, s[8:9]
	v_ashrrev_i32_e32 v71, 31, v70
	global_store_dword v[88:89], v28, off offset:384 sc1
	global_store_dword v[84:85], v27, off offset:384 sc1
	global_store_dword v[82:83], v26, off offset:384 sc1
	global_store_dword v[78:79], v25, off offset:384 sc1
	s_waitcnt vmcnt(17)
	v_fmac_f32_e32 v17, v12, v102
	v_mul_f32_e32 v3, v32, v17
	v_cvt_pk_bf16_f32 v3, v3, s0
	global_store_short v[4:5], v3, off sc1
	v_add_u32_e32 v4, v192, v16
	v_ashrrev_i32_e32 v5, 31, v4
	v_lshl_add_u64 v[4:5], v[4:5], 1, s[8:9]
	s_waitcnt vmcnt(16)
	v_fmac_f32_e32 v2, v13, v102
	v_mul_f32_e32 v3, v32, v2
	v_cvt_pk_bf16_f32 v3, v3, s0
	global_store_short v[4:5], v3, off sc1
	v_add_u32_e32 v4, v193, v16
	v_ashrrev_i32_e32 v5, 31, v4
	v_lshl_add_u64 v[4:5], v[4:5], 1, s[8:9]
	v_xor_b32_e32 v12, 16, v165
	global_store_dword v[72:73], v24, off offset:384 sc1
	global_store_dword v[74:75], v23, off offset:384 sc1
	global_store_dword v[76:77], v22, off offset:384 sc1
	global_store_dword v[80:81], v21, off offset:384 sc1
	global_store_dword v[86:87], v20, off offset:384 sc1
	s_waitcnt vmcnt(20)
	v_fmac_f32_e32 v1, v14, v102
	v_mul_f32_e32 v3, v32, v1
	v_cvt_pk_bf16_f32 v3, v3, s0
	global_store_short v[4:5], v3, off sc1
	v_add_u32_e32 v4, v194, v16
	v_ashrrev_i32_e32 v5, 31, v4
	v_lshl_add_u64 v[10:11], v[4:5], 1, s[8:9]
	v_and_b32_e32 v4, 64, v165
	v_xor_b32_e32 v3, 1, v165
	v_add_u32_e32 v7, 64, v4
	v_cmp_lt_i32_e32 vcc, v3, v7
	v_xor_b32_e32 v4, 2, v165
	s_waitcnt vmcnt(19)
	v_fmac_f32_e32 v0, v15, v102
	v_cndmask_b32_e32 v3, v165, v3, vcc
	v_lshlrev_b32_e32 v3, 2, v3
	ds_bpermute_b32 v5, v3, v106
	v_cmp_lt_i32_e32 vcc, v4, v7
	global_store_dword v[90:91], v19, off offset:384 sc1
	global_store_dword v[92:93], v18, off offset:384 sc1
	v_cndmask_b32_e32 v4, v165, v4, vcc
	v_lshlrev_b32_e32 v4, 2, v4
	s_waitcnt lgkmcnt(0)
	v_add_f32_e32 v6, v106, v5
	ds_bpermute_b32 v8, v4, v6
	v_xor_b32_e32 v5, 4, v165
	v_cmp_lt_i32_e32 vcc, v5, v7
	global_store_dword v[94:95], v17, off offset:384 sc1
	global_store_dword v[96:97], v2, off offset:384 sc1
	v_cndmask_b32_e32 v5, v165, v5, vcc
	v_lshlrev_b32_e32 v5, 2, v5
	s_waitcnt lgkmcnt(0)
	v_add_f32_e32 v8, v6, v8
	ds_bpermute_b32 v9, v5, v8
	v_xor_b32_e32 v6, 8, v165
	v_cmp_lt_i32_e32 vcc, v6, v7
	global_store_dword v[98:99], v1, off offset:384 sc1
	global_store_dword v[100:101], v0, off offset:384 sc1
	v_cndmask_b32_e32 v6, v165, v6, vcc
	v_lshlrev_b32_e32 v6, 2, v6
	s_waitcnt lgkmcnt(0)
	v_add_f32_e32 v8, v8, v9
	ds_bpermute_b32 v9, v6, v8
	v_cmp_lt_i32_e32 vcc, v12, v7
	s_waitcnt lgkmcnt(0)
	v_add_f32_e32 v8, v8, v9
	v_cndmask_b32_e32 v7, v165, v12, vcc
	v_lshlrev_b32_e32 v7, 2, v7
	ds_bpermute_b32 v9, v7, v8
	v_mul_f32_e32 v12, v32, v0
	v_cvt_pk_bf16_f32 v12, v12, s0
	global_store_short v[10:11], v12, off sc1
	s_and_saveexec_b64 s[60:61], s[0:1]
	s_cbranch_execz .LBB0_781
	s_waitcnt lgkmcnt(0)
	v_add_f32_e32 v10, v8, v9
	v_lshl_add_u64 v[8:9], v[70:71], 2, s[58:59]
	global_store_dword v[8:9], v10, off sc1
.LBB0_781:
	s_or_b64 exec, exec, s[60:61]
	v_mul_f32_e32 v8, v63, v63
	v_fmac_f32_e32 v8, v179, v179
	v_fmac_f32_e32 v8, v45, v45
	v_fmac_f32_e32 v8, v28, v28
	s_waitcnt lgkmcnt(0)
	ds_bpermute_b32 v9, v3, v8
	s_waitcnt lgkmcnt(0)
	v_add_f32_e32 v8, v8, v9
	ds_bpermute_b32 v9, v4, v8
	s_waitcnt lgkmcnt(0)
	v_add_f32_e32 v8, v8, v9
	ds_bpermute_b32 v9, v5, v8
	s_waitcnt lgkmcnt(0)
	v_add_f32_e32 v8, v8, v9
	ds_bpermute_b32 v9, v6, v8
	s_waitcnt lgkmcnt(0)
	v_add_f32_e32 v8, v8, v9
	ds_bpermute_b32 v9, v7, v8
	s_and_saveexec_b64 s[60:61], s[0:1]
	s_cbranch_execz .LBB0_783
	s_waitcnt lgkmcnt(0)
	v_add_f32_e32 v10, v8, v9
	v_lshl_add_u64 v[8:9], v[70:71], 2, s[58:59]
	global_store_dword v[8:9], v10, off offset:4 sc1
.LBB0_783:
	s_or_b64 exec, exec, s[60:61]
	v_mul_f32_e32 v8, v62, v62
	v_fmac_f32_e32 v8, v178, v178
	v_fmac_f32_e32 v8, v47, v47
	v_fmac_f32_e32 v8, v27, v27
	s_waitcnt lgkmcnt(0)
	ds_bpermute_b32 v9, v3, v8
	s_waitcnt lgkmcnt(0)
	v_add_f32_e32 v8, v8, v9
	ds_bpermute_b32 v9, v4, v8
	s_waitcnt lgkmcnt(0)
	v_add_f32_e32 v8, v8, v9
	ds_bpermute_b32 v9, v5, v8
	s_waitcnt lgkmcnt(0)
	v_add_f32_e32 v8, v8, v9
	ds_bpermute_b32 v9, v6, v8
	s_waitcnt lgkmcnt(0)
	v_add_f32_e32 v8, v8, v9
	ds_bpermute_b32 v9, v7, v8
	s_and_saveexec_b64 s[60:61], s[0:1]
	s_cbranch_execz .LBB0_785
	s_waitcnt lgkmcnt(0)
	v_add_f32_e32 v10, v8, v9
	v_lshl_add_u64 v[8:9], v[70:71], 2, s[58:59]
	global_store_dword v[8:9], v10, off offset:8 sc1
.LBB0_785:
	s_or_b64 exec, exec, s[60:61]
	v_mul_f32_e32 v8, v61, v61
	v_fmac_f32_e32 v8, v177, v177
	v_fmac_f32_e32 v8, v46, v46
	v_fmac_f32_e32 v8, v26, v26
	s_waitcnt lgkmcnt(0)
	ds_bpermute_b32 v9, v3, v8
	s_waitcnt lgkmcnt(0)
	v_add_f32_e32 v8, v8, v9
	ds_bpermute_b32 v9, v4, v8
	s_waitcnt lgkmcnt(0)
	v_add_f32_e32 v8, v8, v9
	ds_bpermute_b32 v9, v5, v8
	s_waitcnt lgkmcnt(0)
	v_add_f32_e32 v8, v8, v9
	ds_bpermute_b32 v9, v6, v8
	s_waitcnt lgkmcnt(0)
	v_add_f32_e32 v8, v8, v9
	ds_bpermute_b32 v9, v7, v8
	s_and_saveexec_b64 s[60:61], s[0:1]
	s_cbranch_execz .LBB0_787
	s_waitcnt lgkmcnt(0)
	v_add_f32_e32 v10, v8, v9
	v_lshl_add_u64 v[8:9], v[70:71], 2, s[58:59]
	global_store_dword v[8:9], v10, off offset:12 sc1
.LBB0_787:
	s_or_b64 exec, exec, s[60:61]
	v_mul_f32_e32 v8, v60, v60
	v_fmac_f32_e32 v8, v176, v176
	v_fmac_f32_e32 v8, v44, v44
	v_fmac_f32_e32 v8, v25, v25
	s_waitcnt lgkmcnt(0)
	ds_bpermute_b32 v9, v3, v8
	s_waitcnt lgkmcnt(0)
	v_add_f32_e32 v8, v8, v9
	ds_bpermute_b32 v9, v4, v8
	s_waitcnt lgkmcnt(0)
	v_add_f32_e32 v8, v8, v9
	ds_bpermute_b32 v9, v5, v8
	s_waitcnt lgkmcnt(0)
	v_add_f32_e32 v8, v8, v9
	ds_bpermute_b32 v9, v6, v8
	s_waitcnt lgkmcnt(0)
	v_add_f32_e32 v8, v8, v9
	ds_bpermute_b32 v9, v7, v8
	s_and_saveexec_b64 s[60:61], s[0:1]
	s_cbranch_execz .LBB0_789
	s_waitcnt lgkmcnt(0)
	v_add_f32_e32 v10, v8, v9
	v_lshl_add_u64 v[8:9], v[70:71], 2, s[58:59]
	global_store_dword v[8:9], v10, off offset:32 sc1
.LBB0_789:
	s_or_b64 exec, exec, s[60:61]
	v_mul_f32_e32 v8, v59, v59
	v_fmac_f32_e32 v8, v175, v175
	v_fmac_f32_e32 v8, v43, v43
	v_fmac_f32_e32 v8, v24, v24
	s_waitcnt lgkmcnt(0)
	ds_bpermute_b32 v9, v3, v8
	s_waitcnt lgkmcnt(0)
	v_add_f32_e32 v8, v8, v9
	ds_bpermute_b32 v9, v4, v8
	s_waitcnt lgkmcnt(0)
	v_add_f32_e32 v8, v8, v9
	ds_bpermute_b32 v9, v5, v8
	s_waitcnt lgkmcnt(0)
	v_add_f32_e32 v8, v8, v9
	ds_bpermute_b32 v9, v6, v8
	s_waitcnt lgkmcnt(0)
	v_add_f32_e32 v8, v8, v9
	ds_bpermute_b32 v9, v7, v8
	s_and_saveexec_b64 s[60:61], s[0:1]
	s_cbranch_execz .LBB0_791
	s_waitcnt lgkmcnt(0)
	v_add_f32_e32 v10, v8, v9
	v_lshl_add_u64 v[8:9], v[70:71], 2, s[58:59]
	global_store_dword v[8:9], v10, off offset:36 sc1
.LBB0_791:
	s_or_b64 exec, exec, s[60:61]
	v_mul_f32_e32 v8, v58, v58
	v_fmac_f32_e32 v8, v174, v174
	v_fmac_f32_e32 v8, v42, v42
	v_fmac_f32_e32 v8, v23, v23
	s_waitcnt lgkmcnt(0)
	ds_bpermute_b32 v9, v3, v8
	s_waitcnt lgkmcnt(0)
	v_add_f32_e32 v8, v8, v9
	ds_bpermute_b32 v9, v4, v8
	s_waitcnt lgkmcnt(0)
	v_add_f32_e32 v8, v8, v9
	ds_bpermute_b32 v9, v5, v8
	s_waitcnt lgkmcnt(0)
	v_add_f32_e32 v8, v8, v9
	ds_bpermute_b32 v9, v6, v8
	s_waitcnt lgkmcnt(0)
	v_add_f32_e32 v8, v8, v9
	ds_bpermute_b32 v9, v7, v8
	s_and_saveexec_b64 s[60:61], s[0:1]
	s_cbranch_execz .LBB0_793
	s_waitcnt lgkmcnt(0)
	v_add_f32_e32 v10, v8, v9
	v_lshl_add_u64 v[8:9], v[70:71], 2, s[58:59]
	global_store_dword v[8:9], v10, off offset:40 sc1
.LBB0_793:
	s_or_b64 exec, exec, s[60:61]
	v_mul_f32_e32 v8, v57, v57
	v_fmac_f32_e32 v8, v173, v173
	v_fmac_f32_e32 v8, v41, v41
	v_fmac_f32_e32 v8, v22, v22
	s_waitcnt lgkmcnt(0)
	ds_bpermute_b32 v9, v3, v8
	s_waitcnt lgkmcnt(0)
	v_add_f32_e32 v8, v8, v9
	ds_bpermute_b32 v9, v4, v8
	s_waitcnt lgkmcnt(0)
	v_add_f32_e32 v8, v8, v9
	ds_bpermute_b32 v9, v5, v8
	s_waitcnt lgkmcnt(0)
	v_add_f32_e32 v8, v8, v9
	ds_bpermute_b32 v9, v6, v8
	s_waitcnt lgkmcnt(0)
	v_add_f32_e32 v8, v8, v9
	ds_bpermute_b32 v9, v7, v8
	s_and_saveexec_b64 s[60:61], s[0:1]
	s_cbranch_execz .LBB0_795
	s_waitcnt lgkmcnt(0)
	v_add_f32_e32 v10, v8, v9
	v_lshl_add_u64 v[8:9], v[70:71], 2, s[58:59]
	global_store_dword v[8:9], v10, off offset:44 sc1
.LBB0_795:
	s_or_b64 exec, exec, s[60:61]
	v_mul_f32_e32 v8, v56, v56
	v_fmac_f32_e32 v8, v172, v172
	v_fmac_f32_e32 v8, v40, v40
	v_fmac_f32_e32 v8, v21, v21
	s_waitcnt lgkmcnt(0)
	ds_bpermute_b32 v9, v3, v8
	s_waitcnt lgkmcnt(0)
	v_add_f32_e32 v8, v8, v9
	ds_bpermute_b32 v9, v4, v8
	s_waitcnt lgkmcnt(0)
	v_add_f32_e32 v8, v8, v9
	ds_bpermute_b32 v9, v5, v8
	s_waitcnt lgkmcnt(0)
	v_add_f32_e32 v8, v8, v9
	ds_bpermute_b32 v9, v6, v8
	s_waitcnt lgkmcnt(0)
	v_add_f32_e32 v8, v8, v9
	ds_bpermute_b32 v9, v7, v8
	s_and_saveexec_b64 s[60:61], s[0:1]
	s_cbranch_execz .LBB0_797
	s_waitcnt lgkmcnt(0)
	v_add_f32_e32 v10, v8, v9
	v_lshl_add_u64 v[8:9], v[70:71], 2, s[58:59]
	global_store_dword v[8:9], v10, off offset:64 sc1
.LBB0_797:
	s_or_b64 exec, exec, s[60:61]
	v_mul_f32_e32 v8, v55, v55
	v_fmac_f32_e32 v8, v171, v171
	v_fmac_f32_e32 v8, v39, v39
	v_fmac_f32_e32 v8, v20, v20
	s_waitcnt lgkmcnt(0)
	ds_bpermute_b32 v9, v3, v8
	s_waitcnt lgkmcnt(0)
	v_add_f32_e32 v8, v8, v9
	ds_bpermute_b32 v9, v4, v8
	s_waitcnt lgkmcnt(0)
	v_add_f32_e32 v8, v8, v9
	ds_bpermute_b32 v9, v5, v8
	s_waitcnt lgkmcnt(0)
	v_add_f32_e32 v8, v8, v9
	ds_bpermute_b32 v9, v6, v8
	s_waitcnt lgkmcnt(0)
	v_add_f32_e32 v8, v8, v9
	ds_bpermute_b32 v9, v7, v8
	s_and_saveexec_b64 s[60:61], s[0:1]
	s_cbranch_execz .LBB0_799
	s_waitcnt lgkmcnt(0)
	v_add_f32_e32 v10, v8, v9
	v_lshl_add_u64 v[8:9], v[70:71], 2, s[58:59]
	global_store_dword v[8:9], v10, off offset:68 sc1
.LBB0_799:
	s_or_b64 exec, exec, s[60:61]
	v_mul_f32_e32 v8, v54, v54
	v_fmac_f32_e32 v8, v169, v169
	v_fmac_f32_e32 v8, v38, v38
	v_fmac_f32_e32 v8, v19, v19
	s_waitcnt lgkmcnt(0)
	ds_bpermute_b32 v9, v3, v8
	s_waitcnt lgkmcnt(0)
	v_add_f32_e32 v8, v8, v9
	ds_bpermute_b32 v9, v4, v8
	s_waitcnt lgkmcnt(0)
	v_add_f32_e32 v8, v8, v9
	ds_bpermute_b32 v9, v5, v8
	s_waitcnt lgkmcnt(0)
	v_add_f32_e32 v8, v8, v9
	ds_bpermute_b32 v9, v6, v8
	s_waitcnt lgkmcnt(0)
	v_add_f32_e32 v8, v8, v9
	ds_bpermute_b32 v9, v7, v8
	s_and_saveexec_b64 s[60:61], s[0:1]
	s_cbranch_execz .LBB0_801
	s_waitcnt lgkmcnt(0)
	v_add_f32_e32 v10, v8, v9
	v_lshl_add_u64 v[8:9], v[70:71], 2, s[58:59]
	global_store_dword v[8:9], v10, off offset:72 sc1
.LBB0_801:
	s_or_b64 exec, exec, s[60:61]
	v_mul_f32_e32 v8, v53, v53
	v_fmac_f32_e32 v8, v170, v170
	v_fmac_f32_e32 v8, v37, v37
	v_fmac_f32_e32 v8, v18, v18
	s_waitcnt lgkmcnt(0)
	ds_bpermute_b32 v9, v3, v8
	s_waitcnt lgkmcnt(0)
	v_add_f32_e32 v8, v8, v9
	ds_bpermute_b32 v9, v4, v8
	s_waitcnt lgkmcnt(0)
	v_add_f32_e32 v8, v8, v9
	ds_bpermute_b32 v9, v5, v8
	s_waitcnt lgkmcnt(0)
	v_add_f32_e32 v8, v8, v9
	ds_bpermute_b32 v9, v6, v8
	s_waitcnt lgkmcnt(0)
	v_add_f32_e32 v8, v8, v9
	ds_bpermute_b32 v9, v7, v8
	s_and_saveexec_b64 s[60:61], s[0:1]
	s_cbranch_execz .LBB0_803
	s_waitcnt lgkmcnt(0)
	v_add_f32_e32 v10, v8, v9
	v_lshl_add_u64 v[8:9], v[70:71], 2, s[58:59]
	global_store_dword v[8:9], v10, off offset:76 sc1
.LBB0_803:
	s_or_b64 exec, exec, s[60:61]
	v_mul_f32_e32 v8, v52, v52
	v_fmac_f32_e32 v8, v168, v168
	v_fmac_f32_e32 v8, v36, v36
	v_fmac_f32_e32 v8, v17, v17
	s_waitcnt lgkmcnt(0)
	ds_bpermute_b32 v9, v3, v8
	s_waitcnt lgkmcnt(0)
	v_add_f32_e32 v8, v8, v9
	ds_bpermute_b32 v9, v4, v8
	s_waitcnt lgkmcnt(0)
	v_add_f32_e32 v8, v8, v9
	ds_bpermute_b32 v9, v5, v8
	s_waitcnt lgkmcnt(0)
	v_add_f32_e32 v8, v8, v9
	ds_bpermute_b32 v9, v6, v8
	s_waitcnt lgkmcnt(0)
	v_add_f32_e32 v8, v8, v9
	ds_bpermute_b32 v9, v7, v8
	s_and_saveexec_b64 s[60:61], s[0:1]
	s_cbranch_execz .LBB0_805
	s_waitcnt lgkmcnt(0)
	v_add_f32_e32 v10, v8, v9
	v_lshl_add_u64 v[8:9], v[70:71], 2, s[58:59]
	global_store_dword v[8:9], v10, off offset:96 sc1
.LBB0_805:
	s_or_b64 exec, exec, s[60:61]
	v_mul_f32_e32 v8, v51, v51
	v_fmac_f32_e32 v8, v167, v167
	v_fmac_f32_e32 v8, v35, v35
	v_fmac_f32_e32 v8, v2, v2
	ds_bpermute_b32 v2, v3, v8
	s_waitcnt lgkmcnt(0)
	v_add_f32_e32 v2, v8, v2
	ds_bpermute_b32 v8, v4, v2
	s_waitcnt lgkmcnt(0)
	v_add_f32_e32 v2, v2, v8
	ds_bpermute_b32 v8, v5, v2
	s_waitcnt lgkmcnt(0)
	v_add_f32_e32 v2, v2, v8
	ds_bpermute_b32 v8, v6, v2
	s_waitcnt lgkmcnt(0)
	v_add_f32_e32 v2, v2, v8
	ds_bpermute_b32 v8, v7, v2
	s_and_saveexec_b64 s[60:61], s[0:1]
	s_cbranch_execz .LBB0_807
	s_waitcnt lgkmcnt(0)
	v_add_f32_e32 v2, v2, v8
	v_lshl_add_u64 v[8:9], v[70:71], 2, s[58:59]
	global_store_dword v[8:9], v2, off offset:100 sc1
.LBB0_807:
	s_or_b64 exec, exec, s[60:61]
	v_mul_f32_e32 v2, v50, v50
	v_fmac_f32_e32 v2, v166, v166
	v_fmac_f32_e32 v2, v34, v34
	v_fmac_f32_e32 v2, v1, v1
	ds_bpermute_b32 v1, v3, v2
	s_waitcnt lgkmcnt(0)
	v_add_f32_e32 v1, v2, v1
	ds_bpermute_b32 v2, v4, v1
	s_waitcnt lgkmcnt(0)
	v_add_f32_e32 v1, v1, v2
	ds_bpermute_b32 v2, v5, v1
	s_waitcnt lgkmcnt(0)
	v_add_f32_e32 v1, v1, v2
	ds_bpermute_b32 v2, v6, v1
	s_waitcnt lgkmcnt(0)
	v_add_f32_e32 v1, v1, v2
	ds_bpermute_b32 v2, v7, v1
	s_and_saveexec_b64 s[60:61], s[0:1]
	s_cbranch_execz .LBB0_809
	s_waitcnt lgkmcnt(0)
	v_add_f32_e32 v1, v1, v2
	v_lshl_add_u64 v[8:9], v[70:71], 2, s[58:59]
	global_store_dword v[8:9], v1, off offset:104 sc1

.LBB0_811:
	s_cmp_gt_i32 s17, 9
	s_cselect_b64 s[0:1], -1, 0
	s_and_b64 s[4:5], s[4:5], s[0:1]
	s_andn2_b64 vcc, exec, s[4:5]
	s_cbranch_vccnz .LBB0_823
	s_waitcnt vmcnt(0)
	v_or_b32_e32 v0, v201, v200
	s_movk_i32 s3, 0x3ff
	v_and_or_b32 v0, v0, s3, v199
	v_cmp_eq_u32_e32 vcc, 0, v0
	s_waitcnt lgkmcnt(0)
	s_barrier
	s_and_saveexec_b64 s[4:5], vcc
	s_cbranch_execz .LBB0_822
	s_add_u32 s6, s14, 0x5be8c00
	s_addc_u32 s7, s15, 0
	s_lshl_b32 s3, s2, 1
	v_mov_b32_e32 v0, s3
	v_mov_b32_e32 v1, 0x9309
	global_store_short v0, v1, s[6:7] sc1
	s_cmp_lg_u32 s2, 0
	s_cbranch_scc1 .Lgbar_wait_8
	s_lshr_b32 s3, s33, 3
	s_bfm_b64 s[8:9], s3, 0
	s_cmpk_gt_u32 s33, 0x1ff
	s_cselect_b64 s[8:9], -1, s[8:9]
	s_mov_b64 exec, -1
	v_mbcnt_lo_u32_b32 v229, -1, 0
	v_mbcnt_hi_u32_b32 v229, -1, v229
	v_lshlrev_b32_e32 v229, 4, v229
	s_mov_b32 s10, 0x93099309
	s_mov_b64 exec, s[8:9]

.LBB0_823:
	s_cmp_lt_i32 s16, 10
	s_cselect_b64 s[6:7], -1, 0
	s_and_b64 s[0:1], s[6:7], s[0:1]
	s_andn2_b64 vcc, exec, s[0:1]
	s_cbranch_vccnz .LBB0_991
	s_ashr_i32 s0, s2, 31
	s_and_b32 s0, s0, s33
	s_add_i32 s3, s0, s2
	s_cmpk_gt_i32 s3, 0xbff
	s_cbranch_scc1 .LBB0_975
	s_add_u32 s18, s14, 0x5d4e000
	s_addc_u32 s19, s15, 0
	s_add_u32 s10, s14, 0x5bf1000
	s_waitcnt lgkmcnt(0)
	v_lshrrev_b32_e32 v1, 5, v199
	v_bfe_u32 v4, v199, 1, 3
	s_addc_u32 s11, s15, 0
	v_bfe_u32 v2, v199, 5, 1
	v_bitop3_b32 v1, v1, v4, 1 bitop3:0x6c
	s_add_u32 s20, s14, 0x1111f000
	v_lshrrev_b32_e32 v0, 3, v199
	v_lshlrev_b32_e32 v5, 4, v199
	v_lshlrev_b32_e32 v141, 4, v1
	v_bitop3_b32 v1, v2, v4, 2 bitop3:0x36
	s_addc_u32 s21, s15, 0
	v_lshrrev_b32_e32 v3, 1, v199
	v_xor_b32_e32 v6, v5, v199
	v_lshlrev_b32_e32 v7, 11, v0
	s_movk_i32 s0, 0x70
	v_mov_b32_e32 v135, 0
	s_waitcnt vmcnt(22)
	v_lshlrev_b32_e32 v157, 4, v1
	v_bitop3_b32 v1, v2, v4, 4 bitop3:0x36
	s_add_u32 s22, s12, 0x6a00000
	v_and_or_b32 v142, v6, s0, v7
	v_mov_b32_e32 v143, v135
	v_and_b32_e32 v3, 0x1e0, v3
	v_lshlrev_b32_e32 v158, 4, v1
	v_bitop3_b32 v1, v2, v4, 6 bitop3:0x36
	s_addc_u32 s23, s13, 0
	v_lshlrev_b32_e32 v159, 4, v1
	s_waitcnt vmcnt(21)
	v_and_or_b32 v160, v0, 4, v3
	v_lshl_add_u64 v[0:1], s[14:15], 0, v[142:143]
	s_mov_b64 s[0:1], 0x679f000
	s_add_u32 s24, s14, 0x609f000
	v_and_b32_e32 v140, 31, v199
	v_lshl_add_u64 v[144:145], v[0:1], 0, s[0:1]
	s_mov_b64 s[0:1], 0x5a0000
	s_addc_u32 s25, s15, 0
	v_or_b32_e32 v6, v3, v140
	v_or_b32_e32 v162, 32, v140
	s_waitcnt vmcnt(19)
	v_or_b32_e32 v164, 64, v140
	v_or_b32_e32 v166, 0x60, v140
	v_lshl_add_u64 v[146:147], v[0:1], 0, s[0:1]
	s_add_u32 s26, s12, 0x4a00000
	s_waitcnt vmcnt(16)
	v_add_u32_e32 v183, 0, v5
	v_mbcnt_lo_u32_b32 v0, -1, 0
	s_mov_b32 s9, 0
	v_lshl_add_u32 v139, v6, 7, 0
	v_lshl_add_u32 v156, v140, 7, 0
	v_lshlrev_b32_e32 v161, 8, v140
	v_lshlrev_b32_e32 v163, 8, v162
	v_lshlrev_b32_e32 v165, 8, v164
	v_lshlrev_b32_e32 v167, 8, v166
	v_or_b32_e32 v168, 1, v160
	v_or_b32_e32 v169, 2, v160
	v_or_b32_e32 v170, 3, v160
	v_or_b32_e32 v171, 8, v160
	v_or_b32_e32 v172, 9, v160
	v_or_b32_e32 v173, 10, v160
	v_or_b32_e32 v174, 11, v160
	v_or_b32_e32 v175, 16, v160
	v_or_b32_e32 v176, 17, v160
	v_or_b32_e32 v177, 18, v160
	v_or_b32_e32 v178, 19, v160
	v_or_b32_e32 v179, 24, v160
	v_or_b32_e32 v180, 25, v160
	v_or_b32_e32 v181, 26, v160
	v_or_b32_e32 v182, 27, v160
	s_addc_u32 s27, s13, 0
	v_add_u32_e32 v184, 0x4000, v183
	s_mov_b64 s[28:29], 0x10000
	v_add_u32_e32 v185, 0x1000, v183
	v_add_u32_e32 v186, 0x5000, v183
	s_mov_b64 s[30:31], 0x20000
	v_add_u32_e32 v187, 0x2000, v183
	v_add_u32_e32 v188, 0x6000, v183
	s_mov_b64 s[34:35], 0x30000
	v_add_u32_e32 v189, 0x3000, v183
	v_add_u32_e32 v190, 0x7000, v183
	s_mov_b64 s[36:37], 0x679f080
	s_mov_b64 s[38:39], 0x5a0080
	v_add_u32_e32 v191, 0x8000, v183
	v_add_u32_e32 v192, 0xc000, v183
	s_mov_b64 s[40:41], 0x67af080
	v_add_u32_e32 v193, 0x9000, v183
	s_mov_b64 s[42:43], 0x5b0080
	v_add_u32_e32 v194, 0xd000, v183
	s_mov_b64 s[44:45], 0x67bf080
	v_add_u32_e32 v195, 0xa000, v183
	s_mov_b64 s[46:47], 0x5c0080
	s_mov_b64 s[48:49], 0x67cf080
	s_mov_b64 s[50:51], 0x5d0080
	s_mov_b64 s[52:53], 0x679f100
	s_mov_b64 s[54:55], 0x5a0100
	s_mov_b64 s[56:57], 0x67af100
	s_mov_b64 s[58:59], 0x5b0100
	s_mov_b64 s[60:61], 0x67bf100
	s_mov_b64 s[62:63], 0x5c0100
	s_mov_b64 s[64:65], 0x67cf100
	s_mov_b64 s[66:67], 0x5d0100
	s_movk_i32 s76, 0x1100
	s_mov_b32 s77, 0x10000
	s_mov_b32 s78, 0x20000
	s_mov_b32 s79, 0x30000
	s_mov_b32 s80, 0x40000
	s_mov_b32 s81, 0x50000
	s_mov_b32 s82, 0x60000
	s_mov_b32 s83, 0x70000
	v_mov_b32_e32 v196, 0x358637bd
	s_add_i32 s84, 0, 0x120c8
	v_lshlrev_b32_e32 v197, 2, v140
	s_mov_b32 s85, 0x879f000
	v_add_u32_e32 v198, 0xe000, v183
	v_add_u32_e32 v202, 0xb000, v183
	v_add_u32_e32 v203, 0xf000, v183
	v_mbcnt_hi_u32_b32 v204, -1, v0
	s_mov_b32 s49, 0
	s_branch .LBB0_828
.LBB0_826:
	v_ashrrev_i32_e32 v97, 31, v96
	v_lshl_add_u64 v[2:3], v[96:97], 0, v[134:135]
	v_cvt_pk_bf16_f32 v1, v1, s0
	v_lshl_add_u64 v[2:3], v[2:3], 1, s[4:5]
	v_cvt_pk_bf16_f32 v0, v0, s0
	global_store_short v[2:3], v1, off offset:128 sc1
	global_store_short v[2:3], v0, off offset:192 sc1

.LBB0_828:
	s_mul_hi_i32 s0, s3, 0x2aaaaaab
	s_lshr_b32 s1, s0, 31
	s_ashr_i32 s0, s0, 5
	s_add_i32 s0, s0, s1
	s_lshl_b32 s1, s0, 3
	s_mulk_i32 s0, 0xff40
	s_add_i32 s0, s0, s3
	s_ashr_i32 s4, s0, 31
	s_lshr_b32 s4, s4, 29
	s_add_i32 s4, s0, s4
	s_ashr_i32 s86, s4, 3
	s_and_b32 s4, s4, -8
	s_sub_i32 s8, s0, s4
	s_add_i32 s8, s8, s1
	s_lshl_b32 s68, s8, 7
	s_lshl_b32 s0, s86, 7
	s_ashr_i32 s69, s68, 31
	s_ashr_i32 s1, s0, 31
	s_lshl_b64 s[4:5], s[68:69], 11
	s_lshl_b64 s[70:71], s[0:1], 11
	s_cmp_eq_u32 s49, 1
	s_cbranch_scc1 .Lgk_pfhead_p9
	s_lshl_b32 s48, s68, 11
	s_add_u32 s28, s14, s48
	s_addc_u32 s29, s15, 0
	s_add_u32 s28, s28, 0x679f000
	s_addc_u32 s29, s29, 0
	s_add_u32 s30, s28, 0x10000
	s_addc_u32 s31, s29, 0
	s_add_u32 s34, s30, 0x10000
	s_addc_u32 s35, s31, 0
	s_add_u32 s36, s34, 0x10000
	s_addc_u32 s37, s35, 0
	s_lshl_b32 s48, s0, 11
	s_add_u32 s38, s14, s48
	s_addc_u32 s39, s15, 0
	s_add_u32 s38, s38, 0x5a0000
	s_addc_u32 s39, s39, 0
	s_add_u32 s40, s38, 0x10000
	s_addc_u32 s41, s39, 0
	s_add_u32 s42, s40, 0x10000
	s_addc_u32 s43, s41, 0
	s_add_u32 s44, s42, 0x10000
	s_addc_u32 s45, s43, 0
	v_add_u32_e32 v255, v139, v141
	v_add_u32_e32 v188, v156, v141
	v_add_u32_e32 v189, v139, v157
	v_add_u32_e32 v190, v156, v157
	v_add_u32_e32 v191, v139, v158
	v_add_u32_e32 v192, v156, v158
	v_add_u32_e32 v193, v139, v159
	v_add_u32_e32 v194, v156, v159
	v_readfirstlane_b32 s46, v183
	v_mov_b32_e32 v254, v142
	s_mov_b32 m0, s46
	s_nop 0
	global_load_lds_dwordx4 v254, s[28:29]
	s_add_u32 m0, m0, 0x1000
	s_nop 0
	global_load_lds_dwordx4 v254, s[30:31]
	s_add_u32 m0, m0, 0x1000
	s_nop 0
	global_load_lds_dwordx4 v254, s[34:35]
	s_add_u32 m0, m0, 0x1000
	s_nop 0
	global_load_lds_dwordx4 v254, s[36:37]
	s_add_u32 m0, m0, 0x1000
	s_nop 0
	global_load_lds_dwordx4 v254, s[38:39]
	s_add_u32 m0, m0, 0x1000
	s_nop 0
	global_load_lds_dwordx4 v254, s[40:41]
	s_add_u32 m0, m0, 0x1000
	s_nop 0
	global_load_lds_dwordx4 v254, s[42:43]
	s_add_u32 m0, m0, 0x1000
	s_nop 0
	global_load_lds_dwordx4 v254, s[44:45]
	v_add_u32_e32 v254, 0x80, v254
	s_add_u32 m0, s46, 0x8000
	s_nop 0
	global_load_lds_dwordx4 v254, s[28:29]
	s_add_u32 m0, m0, 0x1000
	s_nop 0
	global_load_lds_dwordx4 v254, s[30:31]
	s_add_u32 m0, m0, 0x1000
	s_nop 0
	global_load_lds_dwordx4 v254, s[34:35]
	s_add_u32 m0, m0, 0x1000
	s_nop 0
	global_load_lds_dwordx4 v254, s[36:37]
	s_add_u32 m0, m0, 0x1000
	s_nop 0
	global_load_lds_dwordx4 v254, s[38:39]
	s_add_u32 m0, m0, 0x1000
	s_nop 0
	global_load_lds_dwordx4 v254, s[40:41]
	s_add_u32 m0, m0, 0x1000
	s_nop 0
	global_load_lds_dwordx4 v254, s[42:43]
	s_add_u32 m0, m0, 0x1000
	s_nop 0
	global_load_lds_dwordx4 v254, s[44:45]
	v_add_u32_e32 v254, 0x80, v254
.Lgk_pfhead_p9:
	v_mov_b32_e32 v48, 0
	v_mov_b32_e32 v49, 0
	v_mov_b32_e32 v50, 0
	v_mov_b32_e32 v51, 0
	v_mov_b32_e32 v52, 0
	v_mov_b32_e32 v53, 0
	v_mov_b32_e32 v54, 0
	v_mov_b32_e32 v55, 0
	v_mov_b32_e32 v56, 0
	v_mov_b32_e32 v57, 0
	v_mov_b32_e32 v58, 0
	v_mov_b32_e32 v59, 0
	v_mov_b32_e32 v60, 0
	v_mov_b32_e32 v61, 0
	v_mov_b32_e32 v62, 0
	v_mov_b32_e32 v63, 0
	v_mov_b32_e32 v32, 0
	v_mov_b32_e32 v33, 0
	v_mov_b32_e32 v34, 0
	v_mov_b32_e32 v35, 0
	v_mov_b32_e32 v36, 0
	v_mov_b32_e32 v37, 0
	v_mov_b32_e32 v38, 0
	v_mov_b32_e32 v39, 0
	v_mov_b32_e32 v40, 0
	v_mov_b32_e32 v41, 0
	v_mov_b32_e32 v42, 0
	v_mov_b32_e32 v43, 0
	v_mov_b32_e32 v44, 0
	v_mov_b32_e32 v45, 0
	v_mov_b32_e32 v46, 0
	v_mov_b32_e32 v47, 0
	v_mov_b32_e32 v16, 0
	v_mov_b32_e32 v17, 0
	v_mov_b32_e32 v18, 0
	v_mov_b32_e32 v19, 0
	v_mov_b32_e32 v20, 0
	v_mov_b32_e32 v21, 0
	v_mov_b32_e32 v22, 0
	v_mov_b32_e32 v23, 0
	v_mov_b32_e32 v24, 0
	v_mov_b32_e32 v25, 0
	v_mov_b32_e32 v26, 0
	v_mov_b32_e32 v27, 0
	v_mov_b32_e32 v28, 0
	v_mov_b32_e32 v29, 0
	v_mov_b32_e32 v30, 0
	v_mov_b32_e32 v31, 0
	v_mov_b32_e32 v0, 0
	v_mov_b32_e32 v1, 0
	v_mov_b32_e32 v2, 0
	v_mov_b32_e32 v3, 0
	v_mov_b32_e32 v4, 0
	v_mov_b32_e32 v5, 0
	v_mov_b32_e32 v6, 0
	v_mov_b32_e32 v7, 0
	v_mov_b32_e32 v8, 0
	v_mov_b32_e32 v9, 0
	v_mov_b32_e32 v10, 0
	v_mov_b32_e32 v11, 0
	v_mov_b32_e32 v12, 0
	v_mov_b32_e32 v13, 0
	v_mov_b32_e32 v14, 0
	v_mov_b32_e32 v15, 0
	s_mov_b32 s47, 7
.Lgk_loop_p9:
	s_waitcnt vmcnt(8)
	s_barrier
	ds_read_b128 v[64:67], v255
	ds_read_b128 v[76:79], v188 offset:16384
	ds_read_b128 v[80:83], v188 offset:20480
	ds_read_b128 v[84:87], v188 offset:24576
	ds_read_b128 v[88:91], v188 offset:28672
	ds_read_b128 v[92:95], v189
	ds_read_b128 v[96:99], v190 offset:16384
	ds_read_b128 v[100:103], v190 offset:20480
	ds_read_b128 v[104:107], v190 offset:24576
	ds_read_b128 v[108:111], v190 offset:28672
	ds_read_b128 v[112:115], v191
	ds_read_b128 v[226:229], v192 offset:16384
	ds_read_b128 v[230:233], v192 offset:20480
	ds_read_b128 v[234:237], v192 offset:24576
	ds_read_b128 v[238:241], v192 offset:28672
	ds_read_b128 v[242:245], v193
	ds_read_b128 v[246:249], v194 offset:16384
	ds_read_b128 v[250:253], v194 offset:20480
	ds_read_b128 v[144:147], v194 offset:24576
	ds_read_b128 v[184:187], v194 offset:28672
	s_waitcnt lgkmcnt(0)
	s_barrier
	s_mov_b32 m0, s46
	s_setprio 1
	v_mfma_f32_32x32x16_bf16 v[48:63], v[64:67], v[76:79], v[48:63]
	v_mfma_f32_32x32x16_bf16 v[32:47], v[64:67], v[80:83], v[32:47]
	global_load_lds_dwordx4 v254, s[28:29]
	s_add_u32 m0, m0, 0x1000
	v_mfma_f32_32x32x16_bf16 v[16:31], v[64:67], v[84:87], v[16:31]
	v_mfma_f32_32x32x16_bf16 v[0:15], v[64:67], v[88:91], v[0:15]
	global_load_lds_dwordx4 v254, s[30:31]
	s_add_u32 m0, m0, 0x1000
	v_mfma_f32_32x32x16_bf16 v[48:63], v[92:95], v[96:99], v[48:63]
	v_mfma_f32_32x32x16_bf16 v[32:47], v[92:95], v[100:103], v[32:47]
	global_load_lds_dwordx4 v254, s[34:35]
	s_add_u32 m0, m0, 0x1000
	v_mfma_f32_32x32x16_bf16 v[16:31], v[92:95], v[104:107], v[16:31]
	v_mfma_f32_32x32x16_bf16 v[0:15], v[92:95], v[108:111], v[0:15]
	global_load_lds_dwordx4 v254, s[36:37]
	s_add_u32 m0, m0, 0x1000
	v_mfma_f32_32x32x16_bf16 v[48:63], v[112:115], v[226:229], v[48:63]
	v_mfma_f32_32x32x16_bf16 v[32:47], v[112:115], v[230:233], v[32:47]
	global_load_lds_dwordx4 v254, s[38:39]
	s_add_u32 m0, m0, 0x1000
	v_mfma_f32_32x32x16_bf16 v[16:31], v[112:115], v[234:237], v[16:31]
	v_mfma_f32_32x32x16_bf16 v[0:15], v[112:115], v[238:241], v[0:15]
	global_load_lds_dwordx4 v254, s[40:41]
	s_add_u32 m0, m0, 0x1000
	v_mfma_f32_32x32x16_bf16 v[48:63], v[242:245], v[246:249], v[48:63]
	v_mfma_f32_32x32x16_bf16 v[32:47], v[242:245], v[250:253], v[32:47]
	global_load_lds_dwordx4 v254, s[42:43]
	s_add_u32 m0, m0, 0x1000
	v_mfma_f32_32x32x16_bf16 v[16:31], v[242:245], v[144:147], v[16:31]
	v_mfma_f32_32x32x16_bf16 v[0:15], v[242:245], v[184:187], v[0:15]
	global_load_lds_dwordx4 v254, s[44:45]
	s_setprio 0
	v_add_u32_e32 v254, 0x80, v254
	s_waitcnt vmcnt(8)
	s_barrier
	ds_read_b128 v[64:67], v255 offset:32768
	ds_read_b128 v[76:79], v188 offset:49152
	ds_read_b128 v[80:83], v188 offset:53248
	ds_read_b128 v[84:87], v188 offset:57344
	ds_read_b128 v[88:91], v188 offset:61440
	ds_read_b128 v[92:95], v189 offset:32768
	ds_read_b128 v[96:99], v190 offset:49152
	ds_read_b128 v[100:103], v190 offset:53248
	ds_read_b128 v[104:107], v190 offset:57344
	ds_read_b128 v[108:111], v190 offset:61440
	ds_read_b128 v[112:115], v191 offset:32768
	ds_read_b128 v[226:229], v192 offset:49152
	ds_read_b128 v[230:233], v192 offset:53248
	ds_read_b128 v[234:237], v192 offset:57344
	ds_read_b128 v[238:241], v192 offset:61440
	ds_read_b128 v[242:245], v193 offset:32768
	ds_read_b128 v[246:249], v194 offset:49152
	ds_read_b128 v[250:253], v194 offset:53248
	ds_read_b128 v[144:147], v194 offset:57344
	ds_read_b128 v[184:187], v194 offset:61440
	s_waitcnt lgkmcnt(0)
	s_barrier
	s_add_u32 m0, s46, 0x8000
	s_setprio 1
	v_mfma_f32_32x32x16_bf16 v[48:63], v[64:67], v[76:79], v[48:63]
	v_mfma_f32_32x32x16_bf16 v[32:47], v[64:67], v[80:83], v[32:47]
	global_load_lds_dwordx4 v254, s[28:29]
	s_add_u32 m0, m0, 0x1000
	v_mfma_f32_32x32x16_bf16 v[16:31], v[64:67], v[84:87], v[16:31]
	v_mfma_f32_32x32x16_bf16 v[0:15], v[64:67], v[88:91], v[0:15]
	global_load_lds_dwordx4 v254, s[30:31]
	s_add_u32 m0, m0, 0x1000
	v_mfma_f32_32x32x16_bf16 v[48:63], v[92:95], v[96:99], v[48:63]
	v_mfma_f32_32x32x16_bf16 v[32:47], v[92:95], v[100:103], v[32:47]
	global_load_lds_dwordx4 v254, s[34:35]
	s_add_u32 m0, m0, 0x1000
	v_mfma_f32_32x32x16_bf16 v[16:31], v[92:95], v[104:107], v[16:31]
	v_mfma_f32_32x32x16_bf16 v[0:15], v[92:95], v[108:111], v[0:15]
	global_load_lds_dwordx4 v254, s[36:37]
	s_add_u32 m0, m0, 0x1000
	v_mfma_f32_32x32x16_bf16 v[48:63], v[112:115], v[226:229], v[48:63]
	v_mfma_f32_32x32x16_bf16 v[32:47], v[112:115], v[230:233], v[32:47]
	global_load_lds_dwordx4 v254, s[38:39]
	s_add_u32 m0, m0, 0x1000
	v_mfma_f32_32x32x16_bf16 v[16:31], v[112:115], v[234:237], v[16:31]
	v_mfma_f32_32x32x16_bf16 v[0:15], v[112:115], v[238:241], v[0:15]
	global_load_lds_dwordx4 v254, s[40:41]
	s_add_u32 m0, m0, 0x1000
	v_mfma_f32_32x32x16_bf16 v[48:63], v[242:245], v[246:249], v[48:63]
	v_mfma_f32_32x32x16_bf16 v[32:47], v[242:245], v[250:253], v[32:47]
	global_load_lds_dwordx4 v254, s[42:43]
	s_add_u32 m0, m0, 0x1000
	v_mfma_f32_32x32x16_bf16 v[16:31], v[242:245], v[144:147], v[16:31]
	v_mfma_f32_32x32x16_bf16 v[0:15], v[242:245], v[184:187], v[0:15]
	global_load_lds_dwordx4 v254, s[44:45]
	s_setprio 0
	v_add_u32_e32 v254, 0x80, v254
	s_sub_u32 s47, s47, 1
	s_cmp_lg_u32 s47, 0
	s_cbranch_scc1 .Lgk_loop_p9
	s_add_u32 s50, s3, s33
	s_cmp_gt_u32 s50, 0xbff
	s_cbranch_scc1 .Lgk_tailplain_p9
.LBB0_828_pf_p9:
	s_mul_hi_i32 s52, s50, 0x2aaaaaab
	s_lshr_b32 s53, s52, 31
	s_ashr_i32 s52, s52, 5
	s_add_i32 s52, s52, s53
	s_lshl_b32 s53, s52, 3
	s_mulk_i32 s52, 0xff40
	s_add_i32 s52, s52, s50
	s_ashr_i32 s54, s52, 31
	s_lshr_b32 s54, s54, 29
	s_add_i32 s54, s52, s54
	s_ashr_i32 s60, s54, 3
	s_and_b32 s54, s54, -8
	s_sub_i32 s51, s52, s54
	s_add_i32 s51, s51, s53
	s_lshl_b32 s56, s51, 7
	s_lshl_b32 s52, s60, 7
	s_ashr_i32 s57, s56, 31
	s_ashr_i32 s53, s52, 31
	s_lshl_b64 s[54:55], s[56:57], 11
	s_lshl_b64 s[58:59], s[52:53], 11
	s_lshl_b32 s48, s56, 11
	s_add_u32 s28, s14, s48
	s_addc_u32 s29, s15, 0
	s_add_u32 s28, s28, 0x679f000
	s_addc_u32 s29, s29, 0
	s_add_u32 s30, s28, 0x10000
	s_addc_u32 s31, s29, 0
	s_add_u32 s34, s30, 0x10000
	s_addc_u32 s35, s31, 0
	s_add_u32 s36, s34, 0x10000
	s_addc_u32 s37, s35, 0
	s_lshl_b32 s48, s52, 11
	s_add_u32 s38, s14, s48
	s_addc_u32 s39, s15, 0
	s_add_u32 s38, s38, 0x5a0000
	s_addc_u32 s39, s39, 0
	s_add_u32 s40, s38, 0x10000
	s_addc_u32 s41, s39, 0
	s_add_u32 s42, s40, 0x10000
	s_addc_u32 s43, s41, 0
	s_add_u32 s44, s42, 0x10000
	s_addc_u32 s45, s43, 0
	v_mov_b32_e32 v254, v142
	s_mov_b32 s49, 1
	s_waitcnt vmcnt(8)
	s_barrier
	ds_read_b128 v[64:67], v255
	ds_read_b128 v[76:79], v188 offset:16384
	ds_read_b128 v[80:83], v188 offset:20480
	ds_read_b128 v[84:87], v188 offset:24576
	ds_read_b128 v[88:91], v188 offset:28672
	ds_read_b128 v[92:95], v189
	ds_read_b128 v[96:99], v190 offset:16384
	ds_read_b128 v[100:103], v190 offset:20480
	ds_read_b128 v[104:107], v190 offset:24576
	ds_read_b128 v[108:111], v190 offset:28672
	ds_read_b128 v[112:115], v191
	ds_read_b128 v[226:229], v192 offset:16384
	ds_read_b128 v[230:233], v192 offset:20480
	ds_read_b128 v[234:237], v192 offset:24576
	ds_read_b128 v[238:241], v192 offset:28672
	ds_read_b128 v[242:245], v193
	ds_read_b128 v[246:249], v194 offset:16384
	ds_read_b128 v[250:253], v194 offset:20480
	ds_read_b128 v[144:147], v194 offset:24576
	ds_read_b128 v[184:187], v194 offset:28672
	s_waitcnt lgkmcnt(0)
	s_barrier
	s_mov_b32 m0, s46
	s_setprio 1
	v_mfma_f32_32x32x16_bf16 v[48:63], v[64:67], v[76:79], v[48:63]
	v_mfma_f32_32x32x16_bf16 v[32:47], v[64:67], v[80:83], v[32:47]
	global_load_lds_dwordx4 v254, s[28:29]
	s_add_u32 m0, m0, 0x1000
	v_mfma_f32_32x32x16_bf16 v[16:31], v[64:67], v[84:87], v[16:31]
	v_mfma_f32_32x32x16_bf16 v[0:15], v[64:67], v[88:91], v[0:15]
	global_load_lds_dwordx4 v254, s[30:31]
	s_add_u32 m0, m0, 0x1000
	v_mfma_f32_32x32x16_bf16 v[48:63], v[92:95], v[96:99], v[48:63]
	v_mfma_f32_32x32x16_bf16 v[32:47], v[92:95], v[100:103], v[32:47]
	global_load_lds_dwordx4 v254, s[34:35]
	s_add_u32 m0, m0, 0x1000
	v_mfma_f32_32x32x16_bf16 v[16:31], v[92:95], v[104:107], v[16:31]
	v_mfma_f32_32x32x16_bf16 v[0:15], v[92:95], v[108:111], v[0:15]
	global_load_lds_dwordx4 v254, s[36:37]
	s_add_u32 m0, m0, 0x1000
	v_mfma_f32_32x32x16_bf16 v[48:63], v[112:115], v[226:229], v[48:63]
	v_mfma_f32_32x32x16_bf16 v[32:47], v[112:115], v[230:233], v[32:47]
	global_load_lds_dwordx4 v254, s[38:39]
	s_add_u32 m0, m0, 0x1000
	v_mfma_f32_32x32x16_bf16 v[16:31], v[112:115], v[234:237], v[16:31]
	v_mfma_f32_32x32x16_bf16 v[0:15], v[112:115], v[238:241], v[0:15]
	global_load_lds_dwordx4 v254, s[40:41]
	s_add_u32 m0, m0, 0x1000
	v_mfma_f32_32x32x16_bf16 v[48:63], v[242:245], v[246:249], v[48:63]
	v_mfma_f32_32x32x16_bf16 v[32:47], v[242:245], v[250:253], v[32:47]
	global_load_lds_dwordx4 v254, s[42:43]
	s_add_u32 m0, m0, 0x1000
	v_mfma_f32_32x32x16_bf16 v[16:31], v[242:245], v[144:147], v[16:31]
	v_mfma_f32_32x32x16_bf16 v[0:15], v[242:245], v[184:187], v[0:15]
	global_load_lds_dwordx4 v254, s[44:45]
	s_setprio 0
	v_add_u32_e32 v254, 0x80, v254
	s_waitcnt vmcnt(8)
	s_barrier
	ds_read_b128 v[64:67], v255 offset:32768
	ds_read_b128 v[76:79], v188 offset:49152
	ds_read_b128 v[80:83], v188 offset:53248
	ds_read_b128 v[84:87], v188 offset:57344
	ds_read_b128 v[88:91], v188 offset:61440
	ds_read_b128 v[92:95], v189 offset:32768
	ds_read_b128 v[96:99], v190 offset:49152
	ds_read_b128 v[100:103], v190 offset:53248
	ds_read_b128 v[104:107], v190 offset:57344
	ds_read_b128 v[108:111], v190 offset:61440
	ds_read_b128 v[112:115], v191 offset:32768
	ds_read_b128 v[226:229], v192 offset:49152
	ds_read_b128 v[230:233], v192 offset:53248
	ds_read_b128 v[234:237], v192 offset:57344
	ds_read_b128 v[238:241], v192 offset:61440
	ds_read_b128 v[242:245], v193 offset:32768
	ds_read_b128 v[246:249], v194 offset:49152
	ds_read_b128 v[250:253], v194 offset:53248
	ds_read_b128 v[144:147], v194 offset:57344
	ds_read_b128 v[184:187], v194 offset:61440
	s_waitcnt lgkmcnt(0)
	s_barrier
	s_add_u32 m0, s46, 0x8000
	s_setprio 1
	v_mfma_f32_32x32x16_bf16 v[48:63], v[64:67], v[76:79], v[48:63]
	v_mfma_f32_32x32x16_bf16 v[32:47], v[64:67], v[80:83], v[32:47]
	global_load_lds_dwordx4 v254, s[28:29]
	s_add_u32 m0, m0, 0x1000
	v_mfma_f32_32x32x16_bf16 v[16:31], v[64:67], v[84:87], v[16:31]
	v_mfma_f32_32x32x16_bf16 v[0:15], v[64:67], v[88:91], v[0:15]
	global_load_lds_dwordx4 v254, s[30:31]
	s_add_u32 m0, m0, 0x1000
	v_mfma_f32_32x32x16_bf16 v[48:63], v[92:95], v[96:99], v[48:63]
	v_mfma_f32_32x32x16_bf16 v[32:47], v[92:95], v[100:103], v[32:47]
	global_load_lds_dwordx4 v254, s[34:35]
	s_add_u32 m0, m0, 0x1000
	v_mfma_f32_32x32x16_bf16 v[16:31], v[92:95], v[104:107], v[16:31]
	v_mfma_f32_32x32x16_bf16 v[0:15], v[92:95], v[108:111], v[0:15]
	global_load_lds_dwordx4 v254, s[36:37]
	s_add_u32 m0, m0, 0x1000
	v_mfma_f32_32x32x16_bf16 v[48:63], v[112:115], v[226:229], v[48:63]
	v_mfma_f32_32x32x16_bf16 v[32:47], v[112:115], v[230:233], v[32:47]
	global_load_lds_dwordx4 v254, s[38:39]
	s_add_u32 m0, m0, 0x1000
	v_mfma_f32_32x32x16_bf16 v[16:31], v[112:115], v[234:237], v[16:31]
	v_mfma_f32_32x32x16_bf16 v[0:15], v[112:115], v[238:241], v[0:15]
	global_load_lds_dwordx4 v254, s[40:41]
	s_add_u32 m0, m0, 0x1000
	v_mfma_f32_32x32x16_bf16 v[48:63], v[242:245], v[246:249], v[48:63]
	v_mfma_f32_32x32x16_bf16 v[32:47], v[242:245], v[250:253], v[32:47]
	global_load_lds_dwordx4 v254, s[42:43]
	s_add_u32 m0, m0, 0x1000
	v_mfma_f32_32x32x16_bf16 v[16:31], v[242:245], v[144:147], v[16:31]
	v_mfma_f32_32x32x16_bf16 v[0:15], v[242:245], v[184:187], v[0:15]
	global_load_lds_dwordx4 v254, s[44:45]
	s_setprio 0
	v_add_u32_e32 v254, 0x80, v254
	s_branch .LBB0_832
.Lgk_tailplain_p9:
	s_mov_b32 s49, 0
	s_waitcnt vmcnt(8)
	s_barrier
	ds_read_b128 v[64:67], v255
	ds_read_b128 v[76:79], v188 offset:16384
	ds_read_b128 v[80:83], v188 offset:20480
	ds_read_b128 v[84:87], v188 offset:24576
	ds_read_b128 v[88:91], v188 offset:28672
	ds_read_b128 v[92:95], v189
	ds_read_b128 v[96:99], v190 offset:16384
	ds_read_b128 v[100:103], v190 offset:20480
	ds_read_b128 v[104:107], v190 offset:24576
	ds_read_b128 v[108:111], v190 offset:28672
	ds_read_b128 v[112:115], v191
	ds_read_b128 v[226:229], v192 offset:16384
	ds_read_b128 v[230:233], v192 offset:20480
	ds_read_b128 v[234:237], v192 offset:24576
	ds_read_b128 v[238:241], v192 offset:28672
	ds_read_b128 v[242:245], v193
	ds_read_b128 v[246:249], v194 offset:16384
	ds_read_b128 v[250:253], v194 offset:20480
	ds_read_b128 v[144:147], v194 offset:24576
	ds_read_b128 v[184:187], v194 offset:28672
	s_waitcnt lgkmcnt(0)
	s_barrier
	s_setprio 1
	v_mfma_f32_32x32x16_bf16 v[48:63], v[64:67], v[76:79], v[48:63]
	v_mfma_f32_32x32x16_bf16 v[32:47], v[64:67], v[80:83], v[32:47]
	v_mfma_f32_32x32x16_bf16 v[16:31], v[64:67], v[84:87], v[16:31]
	v_mfma_f32_32x32x16_bf16 v[0:15], v[64:67], v[88:91], v[0:15]
	v_mfma_f32_32x32x16_bf16 v[48:63], v[92:95], v[96:99], v[48:63]
	v_mfma_f32_32x32x16_bf16 v[32:47], v[92:95], v[100:103], v[32:47]
	v_mfma_f32_32x32x16_bf16 v[16:31], v[92:95], v[104:107], v[16:31]
	v_mfma_f32_32x32x16_bf16 v[0:15], v[92:95], v[108:111], v[0:15]
	v_mfma_f32_32x32x16_bf16 v[48:63], v[112:115], v[226:229], v[48:63]
	v_mfma_f32_32x32x16_bf16 v[32:47], v[112:115], v[230:233], v[32:47]
	v_mfma_f32_32x32x16_bf16 v[16:31], v[112:115], v[234:237], v[16:31]
	v_mfma_f32_32x32x16_bf16 v[0:15], v[112:115], v[238:241], v[0:15]
	v_mfma_f32_32x32x16_bf16 v[48:63], v[242:245], v[246:249], v[48:63]
	v_mfma_f32_32x32x16_bf16 v[32:47], v[242:245], v[250:253], v[32:47]
	v_mfma_f32_32x32x16_bf16 v[16:31], v[242:245], v[144:147], v[16:31]
	v_mfma_f32_32x32x16_bf16 v[0:15], v[242:245], v[184:187], v[0:15]
	s_setprio 0
	s_waitcnt vmcnt(0)
	s_barrier
	ds_read_b128 v[64:67], v255 offset:32768
	ds_read_b128 v[76:79], v188 offset:49152
	ds_read_b128 v[80:83], v188 offset:53248
	ds_read_b128 v[84:87], v188 offset:57344
	ds_read_b128 v[88:91], v188 offset:61440
	ds_read_b128 v[92:95], v189 offset:32768
	ds_read_b128 v[96:99], v190 offset:49152
	ds_read_b128 v[100:103], v190 offset:53248
	ds_read_b128 v[104:107], v190 offset:57344
	ds_read_b128 v[108:111], v190 offset:61440
	ds_read_b128 v[112:115], v191 offset:32768
	ds_read_b128 v[226:229], v192 offset:49152
	ds_read_b128 v[230:233], v192 offset:53248
	ds_read_b128 v[234:237], v192 offset:57344
	ds_read_b128 v[238:241], v192 offset:61440
	ds_read_b128 v[242:245], v193 offset:32768
	ds_read_b128 v[246:249], v194 offset:49152
	ds_read_b128 v[250:253], v194 offset:53248
	ds_read_b128 v[144:147], v194 offset:57344
	ds_read_b128 v[184:187], v194 offset:61440
	s_waitcnt lgkmcnt(0)
	s_barrier
	s_setprio 1
	v_mfma_f32_32x32x16_bf16 v[48:63], v[64:67], v[76:79], v[48:63]
	v_mfma_f32_32x32x16_bf16 v[32:47], v[64:67], v[80:83], v[32:47]
	v_mfma_f32_32x32x16_bf16 v[16:31], v[64:67], v[84:87], v[16:31]
	v_mfma_f32_32x32x16_bf16 v[0:15], v[64:67], v[88:91], v[0:15]
	v_mfma_f32_32x32x16_bf16 v[48:63], v[92:95], v[96:99], v[48:63]
	v_mfma_f32_32x32x16_bf16 v[32:47], v[92:95], v[100:103], v[32:47]
	v_mfma_f32_32x32x16_bf16 v[16:31], v[92:95], v[104:107], v[16:31]
	v_mfma_f32_32x32x16_bf16 v[0:15], v[92:95], v[108:111], v[0:15]
	v_mfma_f32_32x32x16_bf16 v[48:63], v[112:115], v[226:229], v[48:63]
	v_mfma_f32_32x32x16_bf16 v[32:47], v[112:115], v[230:233], v[32:47]
	v_mfma_f32_32x32x16_bf16 v[16:31], v[112:115], v[234:237], v[16:31]
	v_mfma_f32_32x32x16_bf16 v[0:15], v[112:115], v[238:241], v[0:15]
	v_mfma_f32_32x32x16_bf16 v[48:63], v[242:245], v[246:249], v[48:63]
	v_mfma_f32_32x32x16_bf16 v[32:47], v[242:245], v[250:253], v[32:47]
	v_mfma_f32_32x32x16_bf16 v[16:31], v[242:245], v[144:147], v[16:31]
	v_mfma_f32_32x32x16_bf16 v[0:15], v[242:245], v[184:187], v[0:15]
	s_setprio 0
	s_branch .LBB0_832

.LBB0_836:
	v_add_u32_e32 v148, s68, v160
	v_ashrrev_i32_e32 v149, 31, v148
	v_lshl_add_u64 v[64:65], v[148:149], 2, s[18:19]
	v_add_co_u32_e32 v66, vcc, 0x10000, v64
	v_or_b32_e32 v150, 8, v148
	s_nop 0
	v_addc_co_u32_e32 v67, vcc, 0, v65, vcc
	global_load_dwordx4 v[92:95], v[64:65], off
	global_load_dwordx4 v[96:99], v[66:67], off
	v_add_co_u32_e32 v66, vcc, 0x20000, v64
	v_ashrrev_i32_e32 v151, 31, v150
	s_nop 0
	v_addc_co_u32_e32 v67, vcc, 0, v65, vcc
	v_add_co_u32_e32 v68, vcc, 0x30000, v64
	v_lshl_add_u64 v[88:89], v[150:151], 2, s[18:19]
	s_nop 0
	v_addc_co_u32_e32 v69, vcc, 0, v65, vcc
	global_load_dwordx4 v[100:103], v[66:67], off
	global_load_dwordx4 v[104:107], v[68:69], off
	v_add_co_u32_e32 v66, vcc, 0x40000, v64
	v_or_b32_e32 v152, 9, v148
	s_nop 0
	v_addc_co_u32_e32 v67, vcc, 0, v65, vcc
	v_add_co_u32_e32 v68, vcc, 0x50000, v64
	v_ashrrev_i32_e32 v153, 31, v152
	s_nop 0
	v_addc_co_u32_e32 v69, vcc, 0, v65, vcc
	global_load_dwordx4 v[108:111], v[66:67], off
	global_load_dwordx4 v[112:115], v[68:69], off
	v_add_co_u32_e32 v66, vcc, 0x60000, v64
	v_lshl_add_u64 v[126:127], v[152:153], 2, s[18:19]
	s_nop 0
	v_addc_co_u32_e32 v67, vcc, 0, v65, vcc
	v_add_co_u32_e32 v64, vcc, 0x70000, v64
	global_load_dwordx4 v[116:119], v[66:67], off
	s_nop 0
	v_addc_co_u32_e32 v65, vcc, 0, v65, vcc
	global_load_dwordx4 v[120:123], v[64:65], off
	v_add_co_u32_e32 v64, vcc, s77, v88
	v_or_b32_e32 v154, 16, v148
	s_nop 0
	v_addc_co_u32_e32 v65, vcc, 0, v89, vcc
	v_add_co_u32_e32 v68, vcc, s78, v88
	global_load_dword v124, v[88:89], off
	s_nop 0
	global_load_dwordx4 v[64:67], v[64:65], off
	v_addc_co_u32_e32 v69, vcc, 0, v89, vcc
	v_add_co_u32_e32 v72, vcc, s79, v88
	v_ashrrev_i32_e32 v155, 31, v154
	s_nop 0
	v_addc_co_u32_e32 v73, vcc, 0, v89, vcc
	v_add_co_u32_e32 v76, vcc, s80, v88
	global_load_dwordx4 v[68:71], v[68:69], off
	s_nop 0
	global_load_dwordx4 v[72:75], v[72:73], off
	v_addc_co_u32_e32 v77, vcc, 0, v89, vcc
	v_add_co_u32_e32 v80, vcc, s81, v88
	s_lshl_b64 s[72:73], s[72:73], 2
	s_nop 0
	v_addc_co_u32_e32 v81, vcc, 0, v89, vcc
	v_add_co_u32_e32 v84, vcc, s82, v88
	global_load_dwordx4 v[76:79], v[76:77], off
	s_nop 0
	global_load_dwordx4 v[80:83], v[80:81], off
	v_addc_co_u32_e32 v85, vcc, 0, v89, vcc
	v_add_co_u32_e32 v88, vcc, s83, v88
	global_load_dwordx4 v[84:87], v[84:85], off
	s_nop 0
	v_addc_co_u32_e32 v89, vcc, 0, v89, vcc
	global_load_dwordx4 v[88:91], v[88:89], off
	s_add_u32 s72, s10, s72
	global_load_dwordx3 v[132:134], v[126:127], off
	s_addc_u32 s73, s11, s73
	s_ashr_i32 s8, s86, 3
	s_waitcnt vmcnt(0)
	v_mov_b32_e32 v126, v92
	v_mov_b32_e32 v128, v96
	v_mov_b32_e32 v130, v104
	v_mov_b32_e32 v127, v108
	v_mov_b32_e32 v129, v112
	v_pk_add_f32 v[126:127], v[126:127], v[128:129]
	v_mov_b32_e32 v108, v93
	v_mov_b32_e32 v112, v97
	v_pk_add_f32 v[92:93], v[108:109], v[112:113]
	v_mov_b32_e32 v128, v100
	v_mov_b32_e32 v100, v106
	v_mov_b32_e32 v129, v116
	v_mov_b32_e32 v116, v101
	v_mov_b32_e32 v131, v120
	v_mov_b32_e32 v120, v105
	v_pk_add_f32 v[96:97], v[116:117], v[120:121]
	v_mov_b32_e32 v101, v122
	v_pk_add_f32 v[92:93], v[92:93], v[96:97]
	v_mov_b32_e32 v96, v98
	v_add_f32_e32 v151, v92, v93
	v_mov_b32_e32 v92, v94
	v_mov_b32_e32 v93, v110
	v_mov_b32_e32 v97, v114
	v_pk_add_f32 v[92:93], v[92:93], v[96:97]
	v_mov_b32_e32 v96, v102
	v_mov_b32_e32 v97, v118
	v_pk_add_f32 v[96:97], v[96:97], v[100:101]
	v_mov_b32_e32 v110, v95
	v_pk_add_f32 v[92:93], v[92:93], v[96:97]
	v_mov_b32_e32 v114, v99
	v_mov_b32_e32 v118, v103
	v_mov_b32_e32 v122, v107
	v_add_f32_e32 v153, v92, v93
	v_pk_add_f32 v[92:93], v[110:111], v[114:115]
	v_pk_add_f32 v[94:95], v[118:119], v[122:123]
	v_mov_b32_e32 v96, v72
	v_pk_add_f32 v[92:93], v[92:93], v[94:95]
	v_mov_b32_e32 v94, v68
	v_add_f32_e32 v205, v92, v93
	v_mov_b32_e32 v92, v64
	v_mov_b32_e32 v125, v76
	v_mov_b32_e32 v93, v80
	v_pk_add_f32 v[92:93], v[124:125], v[92:93]
	v_mov_b32_e32 v80, v65
	v_pk_add_f32 v[128:129], v[128:129], v[130:131]
	v_mov_b32_e32 v95, v84
	v_pk_add_f32 v[126:127], v[126:127], v[128:129]
	v_mov_b32_e32 v84, v69
	v_mov_b32_e32 v97, v88
	v_pk_add_f32 v[94:95], v[94:95], v[96:97]
	v_mov_b32_e32 v76, v132
	v_pk_add_f32 v[92:93], v[92:93], v[94:95]
	v_pk_add_f32 v[76:77], v[76:77], v[80:81]
	v_add_f32_e32 v225, v92, v93
	v_lshl_add_u64 v[92:93], v[154:155], 2, s[18:19]
	v_add_co_u32_e32 v80, vcc, s77, v92
	global_load_dword v64, v[92:93], off
	s_nop 0
	v_addc_co_u32_e32 v81, vcc, 0, v93, vcc
	v_add_co_u32_e32 v94, vcc, s78, v92
	v_mov_b32_e32 v88, v73
	s_nop 0
	v_addc_co_u32_e32 v95, vcc, 0, v93, vcc
	global_load_dwordx4 v[206:209], v[80:81], off
	global_load_dwordx4 v[210:213], v[94:95], off
	v_add_co_u32_e32 v80, vcc, s79, v92
	v_pk_add_f32 v[68:69], v[84:85], v[88:89]
	s_nop 0
	v_addc_co_u32_e32 v81, vcc, 0, v93, vcc
	v_add_co_u32_e32 v94, vcc, s80, v92
	v_or_b32_e32 v84, 24, v148
	s_nop 0
	v_addc_co_u32_e32 v95, vcc, 0, v93, vcc
	global_load_dwordx4 v[104:107], v[80:81], off
	global_load_dwordx4 v[214:217], v[94:95], off
	v_add_co_u32_e32 v80, vcc, s81, v92
	v_ashrrev_i32_e32 v85, 31, v84
	s_nop 0
	v_addc_co_u32_e32 v81, vcc, 0, v93, vcc
	v_add_co_u32_e32 v94, vcc, s82, v92
	v_lshl_add_u64 v[72:73], v[84:85], 2, s[18:19]
	s_nop 0
	v_addc_co_u32_e32 v95, vcc, 0, v93, vcc
	global_load_dwordx4 v[218:221], v[80:81], off
	global_load_dwordx4 v[120:123], v[94:95], off
	v_add_co_u32_e32 v80, vcc, s83, v92
	v_pk_add_f32 v[68:69], v[76:77], v[68:69]
	s_nop 0
	v_addc_co_u32_e32 v81, vcc, 0, v93, vcc
	global_load_dwordx4 v[128:131], v[80:81], off
	v_or_b32_e32 v80, 17, v148
	v_ashrrev_i32_e32 v81, 31, v80
	v_lshl_add_u64 v[92:93], v[80:81], 2, s[18:19]
	global_load_dwordx3 v[222:224], v[92:93], off
	v_add_co_u32_e32 v76, vcc, s77, v72
	v_add_f32_e32 v149, v126, v127
	s_nop 0
	v_addc_co_u32_e32 v77, vcc, 0, v73, vcc
	global_load_dword v132, v[72:73], off
	global_load_dwordx4 v[92:95], v[76:77], off
	v_add_co_u32_e32 v76, vcc, s78, v72
	v_add_f32_e32 v81, v68, v69
	s_nop 0
	v_addc_co_u32_e32 v77, vcc, 0, v73, vcc
	v_add_co_u32_e32 v88, vcc, s79, v72
	s_waitcnt vmcnt(6)
	v_mov_b32_e32 v65, v214
	v_addc_co_u32_e32 v89, vcc, 0, v73, vcc
	global_load_dwordx4 v[96:99], v[76:77], off
	global_load_dwordx4 v[100:103], v[88:89], off
	v_add_co_u32_e32 v76, vcc, s80, v72
	s_waitcnt vmcnt(4)
	v_mov_b32_e32 v214, v222
	v_addc_co_u32_e32 v77, vcc, 0, v73, vcc
	v_add_co_u32_e32 v88, vcc, s81, v72
	s_nop 1
	v_addc_co_u32_e32 v89, vcc, 0, v73, vcc
	global_load_dwordx4 v[108:111], v[76:77], off
	global_load_dwordx4 v[112:115], v[88:89], off
	v_add_co_u32_e32 v76, vcc, s82, v72
	v_or_b32_e32 v88, 25, v148
	s_nop 0
	v_addc_co_u32_e32 v77, vcc, 0, v73, vcc
	v_add_co_u32_e32 v72, vcc, s83, v72
	global_load_dwordx4 v[116:119], v[76:77], off
	s_nop 0
	v_addc_co_u32_e32 v73, vcc, 0, v73, vcc
	global_load_dwordx4 v[124:127], v[72:73], off
	v_ashrrev_i32_e32 v89, 31, v88
	v_lshl_add_u64 v[68:69], v[88:89], 2, s[18:19]
	global_load_dwordx3 v[136:138], v[68:69], off
	v_mov_b32_e32 v68, v133
	v_mov_b32_e32 v69, v78
	v_mov_b32_e32 v72, v66
	v_mov_b32_e32 v73, v82
	v_pk_add_f32 v[68:69], v[68:69], v[72:73]
	v_mov_b32_e32 v72, v70
	v_mov_b32_e32 v73, v86
	v_mov_b32_e32 v76, v74
	v_mov_b32_e32 v77, v90
	v_pk_add_f32 v[72:73], v[72:73], v[76:77]
	v_mov_b32_e32 v78, v134
	v_pk_add_f32 v[68:69], v[68:69], v[72:73]
	v_mov_b32_e32 v82, v67
	v_mov_b32_e32 v86, v71
	v_mov_b32_e32 v90, v75
	v_add_f32_e32 v72, v68, v69
	v_pk_add_f32 v[66:67], v[78:79], v[82:83]
	v_pk_add_f32 v[68:69], v[86:87], v[90:91]
	s_waitcnt vmcnt(5)
	v_mov_b32_e32 v70, v100
	v_pk_add_f32 v[66:67], v[66:67], v[68:69]
	v_mov_b32_e32 v68, v104
	v_add_f32_e32 v73, v66, v67
	v_mov_b32_e32 v66, v206
	v_mov_b32_e32 v67, v218
	v_pk_add_f32 v[64:65], v[64:65], v[66:67]
	v_mov_b32_e32 v66, v210
	v_mov_b32_e32 v67, v120
	v_mov_b32_e32 v69, v128
	v_pk_add_f32 v[66:67], v[66:67], v[68:69]
	v_mov_b32_e32 v218, v207
	v_pk_add_f32 v[64:65], v[64:65], v[66:67]
	v_mov_b32_e32 v120, v211
	v_mov_b32_e32 v128, v105
	v_add_f32_e32 v74, v64, v65
	v_pk_add_f32 v[64:65], v[214:215], v[218:219]
	v_pk_add_f32 v[66:67], v[120:121], v[128:129]
	v_mov_b32_e32 v68, v106
	v_pk_add_f32 v[64:65], v[64:65], v[66:67]
	v_mov_b32_e32 v66, v208
	v_add_f32_e32 v75, v64, v65
	v_mov_b32_e32 v64, v223
	v_mov_b32_e32 v65, v216
	v_mov_b32_e32 v67, v220
	v_pk_add_f32 v[64:65], v[64:65], v[66:67]
	v_mov_b32_e32 v66, v212
	v_mov_b32_e32 v67, v122
	v_mov_b32_e32 v69, v130
	v_pk_add_f32 v[66:67], v[66:67], v[68:69]
	v_mov_b32_e32 v216, v224
	v_pk_add_f32 v[64:65], v[64:65], v[66:67]
	v_or_b32_e32 v66, s0, v140
	v_ashrrev_i32_e32 v67, 31, v66
	v_lshl_add_u64 v[66:67], v[66:67], 2, s[72:73]
	global_load_dword v91, v[66:67], off
	global_load_dword v90, v[66:67], off offset:128
	global_load_dword v105, v[66:67], off offset:256
	global_load_dword v104, v[66:67], off offset:384
	v_mov_b32_e32 v220, v209
	v_mov_b32_e32 v122, v213
	v_mov_b32_e32 v130, v107
	v_add_f32_e32 v76, v64, v65
	v_pk_add_f32 v[64:65], v[216:217], v[220:221]
	v_pk_add_f32 v[68:69], v[122:123], v[130:131]
	s_waitcnt vmcnt(8)
	v_mov_b32_e32 v133, v108
	v_pk_add_f32 v[64:65], v[64:65], v[68:69]
	v_mov_b32_e32 v68, v96
	v_add_f32_e32 v77, v64, v65
	v_mov_b32_e32 v64, v92
	s_waitcnt vmcnt(7)
	v_mov_b32_e32 v65, v112
	s_waitcnt vmcnt(6)
	v_mov_b32_e32 v69, v116
	s_waitcnt vmcnt(5)
	v_mov_b32_e32 v71, v124
	v_pk_add_f32 v[64:65], v[132:133], v[64:65]
	v_pk_add_f32 v[68:69], v[68:69], v[70:71]
	s_waitcnt vmcnt(4)
	v_mov_b32_e32 v108, v136
	v_pk_add_f32 v[64:65], v[64:65], v[68:69]
	v_mov_b32_e32 v112, v93
	v_mov_b32_e32 v116, v97
	v_mov_b32_e32 v124, v101
	v_add_f32_e32 v78, v64, v65
	v_pk_add_f32 v[64:65], v[108:109], v[112:113]
	v_pk_add_f32 v[68:69], v[116:117], v[124:125]
	v_mov_b32_e32 v70, v102
	v_pk_add_f32 v[64:65], v[64:65], v[68:69]
	v_mov_b32_e32 v68, v94
	v_add_f32_e32 v79, v64, v65
	v_mov_b32_e32 v64, v137
	v_mov_b32_e32 v65, v110
	v_mov_b32_e32 v69, v114
	v_pk_add_f32 v[64:65], v[64:65], v[68:69]
	v_mov_b32_e32 v68, v98
	v_mov_b32_e32 v69, v118
	v_mov_b32_e32 v71, v126
	v_pk_add_f32 v[68:69], v[68:69], v[70:71]
	v_mov_b32_e32 v110, v138
	v_pk_add_f32 v[64:65], v[64:65], v[68:69]
	v_mov_b32_e32 v114, v95
	v_mov_b32_e32 v118, v99
	v_mov_b32_e32 v126, v103
	v_add_f32_e32 v68, v64, v65
	v_pk_add_f32 v[64:65], v[110:111], v[114:115]
	v_pk_add_f32 v[66:67], v[118:119], v[126:127]
	s_and_b32 s72, s86, 7
	v_pk_add_f32 v[64:65], v[64:65], v[66:67]
	s_cmp_gt_i32 s8, 1
	v_add_f32_e32 v64, v64, v65
	v_fmamk_f32 v65, v149, 0x3a800000, v196
	v_rsq_f32_e32 v92, v65
	v_fmamk_f32 v65, v151, 0x3a800000, v196
	v_rsq_f32_e32 v94, v65
	v_fmamk_f32 v65, v153, 0x3a800000, v196
	v_rsq_f32_e32 v96, v65
	v_fmamk_f32 v65, v205, 0x3a800000, v196
	v_rsq_f32_e32 v98, v65
	v_fmamk_f32 v65, v225, 0x3a800000, v196
	v_rsq_f32_e32 v100, v65
	v_fmamk_f32 v65, v81, 0x3a800000, v196
	v_rsq_f32_e32 v102, v65
	v_fmamk_f32 v65, v72, 0x3a800000, v196
	v_rsq_f32_e32 v106, v65
	v_fmamk_f32 v65, v73, 0x3a800000, v196
	v_rsq_f32_e32 v108, v65
	v_fmamk_f32 v65, v74, 0x3a800000, v196
	v_rsq_f32_e32 v110, v65
	v_fmamk_f32 v65, v75, 0x3a800000, v196
	v_rsq_f32_e32 v112, v65
	v_fmamk_f32 v65, v76, 0x3a800000, v196
	v_rsq_f32_e32 v114, v65
	v_fmamk_f32 v65, v77, 0x3a800000, v196
	v_rsq_f32_e32 v116, v65
	v_fmamk_f32 v65, v78, 0x3a800000, v196
	v_rsq_f32_e32 v118, v65
	v_fmamk_f32 v65, v79, 0x3a800000, v196
	v_rsq_f32_e32 v120, v65
	v_fmamk_f32 v65, v68, 0x3a800000, v196
	v_fmamk_f32 v64, v64, 0x3a800000, v196
	v_rsq_f32_e32 v122, v65
	v_rsq_f32_e32 v124, v64
	v_mov_b32_e32 v64, v32
	v_mov_b32_e32 v65, v48
	v_mov_b32_e32 v48, v33
	v_mov_b32_e32 v32, v34
	v_mov_b32_e32 v33, v50
	s_waitcnt vmcnt(2)
	v_pk_fma_f32 v[78:79], v[32:33], v[96:97], v[90:91] op_sel_hi:[1,0,1]
	v_mov_b32_e32 v32, v36
	v_mov_b32_e32 v33, v52
	v_pk_fma_f32 v[70:71], v[32:33], v[100:101], v[90:91] op_sel_hi:[1,0,1]
	v_mov_b32_e32 v32, v38
	v_mov_b32_e32 v33, v54
	v_pk_fma_f32 v[76:77], v[32:33], v[106:107], v[90:91] op_sel_hi:[1,0,1]
	v_mov_b32_e32 v32, v40
	v_mov_b32_e32 v33, v56
	v_pk_fma_f32 v[66:67], v[32:33], v[110:111], v[90:91] op_sel_hi:[1,0,1]
	v_mov_b32_e32 v56, v41
	v_mov_b32_e32 v32, v42
	v_mov_b32_e32 v33, v58
	v_pk_fma_f32 v[86:87], v[64:65], v[92:93], v[90:91] op_sel_hi:[1,0,1]
	v_mov_b32_e32 v52, v37
	v_pk_fma_f32 v[64:65], v[56:57], v[112:113], v[90:91] op_sel_hi:[1,0,1]
	v_pk_fma_f32 v[56:57], v[32:33], v[114:115], v[90:91] op_sel_hi:[1,0,1]
	v_mov_b32_e32 v32, v44
	v_mov_b32_e32 v33, v60
	v_pk_fma_f32 v[72:73], v[52:53], v[102:103], v[90:91] op_sel_hi:[1,0,1]
	v_pk_fma_f32 v[52:53], v[32:33], v[118:119], v[90:91] op_sel_hi:[1,0,1]
	v_mov_b32_e32 v32, v46
	v_mov_b32_e32 v33, v62
	v_pk_fma_f32 v[82:83], v[48:49], v[94:95], v[90:91] op_sel_hi:[1,0,1]
	v_pk_fma_f32 v[48:49], v[32:33], v[122:123], v[90:91] op_sel_hi:[1,0,1]
	v_mov_b32_e32 v32, v0
	v_mov_b32_e32 v33, v16
	v_mov_b32_e32 v16, v1
	v_mov_b32_e32 v0, v2
	v_mov_b32_e32 v1, v18
	s_waitcnt vmcnt(0)
	v_pk_fma_f32 v[40:41], v[0:1], v[96:97], v[104:105] op_sel_hi:[1,0,1]
	v_mov_b32_e32 v0, v4
	v_mov_b32_e32 v1, v20
	v_pk_fma_f32 v[36:37], v[0:1], v[100:101], v[104:105] op_sel_hi:[1,0,1]
	v_mov_b32_e32 v0, v6
	v_mov_b32_e32 v1, v22
	v_mov_b32_e32 v60, v45
	v_pk_fma_f32 v[44:45], v[32:33], v[92:93], v[104:105] op_sel_hi:[1,0,1]
	v_mov_b32_e32 v20, v5
	v_pk_fma_f32 v[32:33], v[0:1], v[106:107], v[104:105] op_sel_hi:[1,0,1]
	v_mov_b32_e32 v0, v8
	v_mov_b32_e32 v1, v24
	v_mov_b32_e32 v50, v35
	v_pk_fma_f32 v[34:35], v[20:21], v[102:103], v[104:105] op_sel_hi:[1,0,1]
	v_pk_fma_f32 v[20:21], v[0:1], v[110:111], v[104:105] op_sel_hi:[1,0,1]
	v_mov_b32_e32 v0, v10
	v_mov_b32_e32 v1, v26
	v_mov_b32_e32 v58, v43
	v_pk_fma_f32 v[42:43], v[16:17], v[94:95], v[104:105] op_sel_hi:[1,0,1]
	v_pk_fma_f32 v[16:17], v[0:1], v[114:115], v[104:105] op_sel_hi:[1,0,1]
	v_mov_b32_e32 v0, v12
	v_mov_b32_e32 v1, v28
	v_mov_b32_e32 v54, v39
	v_mov_b32_e32 v62, v47
	v_mov_b32_e32 v18, v3
	v_mov_b32_e32 v22, v7
	v_mov_b32_e32 v24, v9
	v_mov_b32_e32 v26, v11
	v_pk_fma_f32 v[6:7], v[0:1], v[118:119], v[104:105] op_sel_hi:[1,0,1]
	v_mov_b32_e32 v28, v13
	v_mov_b32_e32 v0, v14
	v_mov_b32_e32 v1, v30
	v_mov_b32_e32 v30, v15
	v_pk_fma_f32 v[74:75], v[50:51], v[98:99], v[90:91] op_sel_hi:[1,0,1]
	v_pk_fma_f32 v[68:69], v[54:55], v[108:109], v[90:91] op_sel_hi:[1,0,1]
	v_pk_fma_f32 v[54:55], v[58:59], v[116:117], v[90:91] op_sel_hi:[1,0,1]
	v_pk_fma_f32 v[50:51], v[60:61], v[120:121], v[90:91] op_sel_hi:[1,0,1]
	v_pk_fma_f32 v[46:47], v[62:63], v[124:125], v[90:91] op_sel_hi:[1,0,1]
	v_pk_fma_f32 v[38:39], v[18:19], v[98:99], v[104:105] op_sel_hi:[1,0,1]
	v_pk_fma_f32 v[22:23], v[22:23], v[108:109], v[104:105] op_sel_hi:[1,0,1]
	v_pk_fma_f32 v[18:19], v[24:25], v[112:113], v[104:105] op_sel_hi:[1,0,1]
	v_pk_fma_f32 v[8:9], v[26:27], v[116:117], v[104:105] op_sel_hi:[1,0,1]
	v_pk_fma_f32 v[4:5], v[28:29], v[120:121], v[104:105] op_sel_hi:[1,0,1]
	v_pk_fma_f32 v[2:3], v[0:1], v[122:123], v[104:105] op_sel_hi:[1,0,1]
	v_pk_fma_f32 v[0:1], v[30:31], v[124:125], v[104:105] op_sel_hi:[1,0,1]
	s_mov_b64 s[0:1], -1
	s_cbranch_scc0 .LBB0_846
	s_and_b64 s[0:1], s[4:5], exec
	s_cselect_b32 s0, 0x100, 0
	s_add_i32 s0, s69, s0
	v_add_u32_e32 v27, s0, v160
	s_lshl_b32 s0, s87, 18
	s_lshl_b32 s1, s72, 15
	s_or_b32 s75, s0, s1
	s_lshl_b32 s0, s87, 10
	s_lshl_b32 s73, s72, 7
	s_or_b32 s87, s0, s73
	v_or_b32_e32 v29, s87, v140
	v_mul_lo_u32 v29, v29, s76
	v_or_b32_e32 v28, s75, v161
	v_add_u32_e32 v29, 0x800000, v29
	v_cndmask_b32_e64 v60, v28, v29, s[4:5]
	v_add_u32_e32 v28, v60, v27
	v_ashrrev_i32_e32 v29, 31, v28
	v_cvt_pk_bf16_f32 v30, v87, v83
	v_cvt_pk_bf16_f32 v31, v79, v75
	v_lshl_add_u64 v[28:29], v[28:29], 1, s[20:21]
	global_store_dwordx2 v[28:29], v[30:31], off sc1
	v_or_b32_e32 v28, 8, v27
	v_add_u32_e32 v30, v60, v28
	v_ashrrev_i32_e32 v31, 31, v30
	v_cvt_pk_bf16_f32 v58, v71, v73
	v_cvt_pk_bf16_f32 v59, v77, v69
	v_lshl_add_u64 v[30:31], v[30:31], 1, s[20:21]
	v_or_b32_e32 v29, 16, v27
	global_store_dwordx2 v[30:31], v[58:59], off sc1
	v_add_u32_e32 v30, v60, v29
	v_ashrrev_i32_e32 v31, 31, v30
	v_cvt_pk_bf16_f32 v58, v67, v65
	v_cvt_pk_bf16_f32 v59, v57, v55
	v_lshl_add_u64 v[30:31], v[30:31], 1, s[20:21]
	global_store_dwordx2 v[30:31], v[58:59], off sc1
	v_or_b32_e32 v30, 24, v27
	v_add_u32_e32 v58, v60, v30
	v_ashrrev_i32_e32 v59, 31, v58
	v_cndmask_b32_e64 v31, 0, 1, s[70:71]
	v_or_b32_e32 v26, 1, v148
	v_or_b32_e32 v25, 2, v148
	v_or_b32_e32 v24, 3, v148
	v_or_b32_e32 v15, 10, v148
	v_or_b32_e32 v14, 11, v148
	v_or_b32_e32 v13, 18, v148
	v_or_b32_e32 v12, 19, v148
	v_or_b32_e32 v11, 26, v148
	v_or_b32_e32 v10, 27, v148
	v_cvt_pk_bf16_f32 v60, v53, v51
	v_cvt_pk_bf16_f32 v61, v49, v47
	v_lshl_add_u64 v[58:59], v[58:59], 1, s[20:21]
	v_cmp_ne_u32_e64 s[0:1], 1, v31
	s_andn2_b64 vcc, exec, s[70:71]
	global_store_dwordx2 v[58:59], v[60:61], off sc1
	s_cbranch_vccnz .LBB0_839
	v_or_b32_e32 v31, s73, v140
	v_lshl_or_b32 v58, v148, 10, v31
	v_ashrrev_i32_e32 v59, 31, v58
	v_lshl_add_u64 v[58:59], v[58:59], 2, s[22:23]
	global_store_dword v[58:59], v87, off sc1
	v_lshl_or_b32 v58, v26, 10, v31
	v_ashrrev_i32_e32 v59, 31, v58
	v_lshl_add_u64 v[58:59], v[58:59], 2, s[22:23]
	global_store_dword v[58:59], v83, off sc1
	v_lshl_or_b32 v58, v25, 10, v31
	v_ashrrev_i32_e32 v59, 31, v58
	v_lshl_add_u64 v[58:59], v[58:59], 2, s[22:23]
	global_store_dword v[58:59], v79, off sc1
	v_lshl_or_b32 v58, v24, 10, v31
	v_ashrrev_i32_e32 v59, 31, v58
	v_lshl_add_u64 v[58:59], v[58:59], 2, s[22:23]
	global_store_dword v[58:59], v75, off sc1
	v_lshl_or_b32 v58, v150, 10, v31
	v_ashrrev_i32_e32 v59, 31, v58
	v_lshl_add_u64 v[58:59], v[58:59], 2, s[22:23]
	global_store_dword v[58:59], v71, off sc1
	v_lshl_or_b32 v58, v152, 10, v31
	v_ashrrev_i32_e32 v59, 31, v58
	v_lshl_add_u64 v[58:59], v[58:59], 2, s[22:23]
	global_store_dword v[58:59], v73, off sc1
	v_lshl_or_b32 v58, v15, 10, v31
	v_ashrrev_i32_e32 v59, 31, v58
	v_lshl_add_u64 v[58:59], v[58:59], 2, s[22:23]
	global_store_dword v[58:59], v77, off sc1
	v_lshl_or_b32 v58, v14, 10, v31
	v_ashrrev_i32_e32 v59, 31, v58
	v_lshl_add_u64 v[58:59], v[58:59], 2, s[22:23]
	global_store_dword v[58:59], v69, off sc1
	v_lshl_or_b32 v58, v154, 10, v31
	v_ashrrev_i32_e32 v59, 31, v58
	v_lshl_add_u64 v[58:59], v[58:59], 2, s[22:23]
	global_store_dword v[58:59], v67, off sc1
	v_lshl_or_b32 v58, v80, 10, v31
	v_ashrrev_i32_e32 v59, 31, v58
	v_lshl_add_u64 v[58:59], v[58:59], 2, s[22:23]
	global_store_dword v[58:59], v65, off sc1
	v_lshl_or_b32 v58, v13, 10, v31
	v_ashrrev_i32_e32 v59, 31, v58
	v_lshl_add_u64 v[58:59], v[58:59], 2, s[22:23]
	global_store_dword v[58:59], v57, off sc1
	v_lshl_or_b32 v58, v12, 10, v31
	v_ashrrev_i32_e32 v59, 31, v58
	v_lshl_add_u64 v[58:59], v[58:59], 2, s[22:23]
	global_store_dword v[58:59], v55, off sc1
	v_lshl_or_b32 v58, v84, 10, v31
	v_ashrrev_i32_e32 v59, 31, v58
	v_lshl_add_u64 v[58:59], v[58:59], 2, s[22:23]
	global_store_dword v[58:59], v53, off sc1
	v_lshl_or_b32 v58, v88, 10, v31
	v_ashrrev_i32_e32 v59, 31, v58
	v_lshl_add_u64 v[58:59], v[58:59], 2, s[22:23]
	global_store_dword v[58:59], v51, off sc1
	v_lshl_or_b32 v58, v11, 10, v31
	v_ashrrev_i32_e32 v59, 31, v58
	v_lshl_add_u64 v[58:59], v[58:59], 2, s[22:23]
	global_store_dword v[58:59], v49, off sc1
	v_lshl_or_b32 v58, v10, 10, v31
	v_ashrrev_i32_e32 v59, 31, v58
	v_lshl_add_u64 v[58:59], v[58:59], 2, s[22:23]
	global_store_dword v[58:59], v47, off sc1
.LBB0_839:
	v_or_b32_e32 v58, s87, v162
	v_mul_lo_u32 v58, v58, s76
	v_or_b32_e32 v31, s75, v163
	v_add_u32_e32 v58, 0x800000, v58
	v_cndmask_b32_e64 v31, v31, v58, s[4:5]
	v_add_u32_e32 v58, v31, v27
	v_ashrrev_i32_e32 v59, 31, v58
	v_cvt_pk_bf16_f32 v60, v86, v82
	v_cvt_pk_bf16_f32 v61, v78, v74
	v_lshl_add_u64 v[58:59], v[58:59], 1, s[20:21]
	global_store_dwordx2 v[58:59], v[60:61], off sc1
	v_add_u32_e32 v58, v31, v28
	v_ashrrev_i32_e32 v59, 31, v58
	v_cvt_pk_bf16_f32 v60, v70, v72
	v_cvt_pk_bf16_f32 v61, v76, v68
	v_lshl_add_u64 v[58:59], v[58:59], 1, s[20:21]
	global_store_dwordx2 v[58:59], v[60:61], off sc1
	v_add_u32_e32 v58, v31, v29
	v_ashrrev_i32_e32 v59, 31, v58
	v_cvt_pk_bf16_f32 v60, v66, v64
	v_cvt_pk_bf16_f32 v61, v56, v54
	v_lshl_add_u64 v[58:59], v[58:59], 1, s[20:21]
	global_store_dwordx2 v[58:59], v[60:61], off sc1
	v_add_u32_e32 v58, v31, v30
	v_ashrrev_i32_e32 v59, 31, v58
	v_cvt_pk_bf16_f32 v60, v52, v50
	v_cvt_pk_bf16_f32 v61, v48, v46
	v_lshl_add_u64 v[58:59], v[58:59], 1, s[20:21]
	s_and_b64 vcc, exec, s[0:1]
	global_store_dwordx2 v[58:59], v[60:61], off sc1
	s_cbranch_vccnz .LBB0_841
	v_or_b32_e32 v31, s73, v162
	v_lshl_or_b32 v58, v148, 10, v31
	v_ashrrev_i32_e32 v59, 31, v58
	v_lshl_add_u64 v[58:59], v[58:59], 2, s[22:23]
	global_store_dword v[58:59], v86, off sc1
	v_lshl_or_b32 v58, v26, 10, v31
	v_ashrrev_i32_e32 v59, 31, v58
	v_lshl_add_u64 v[58:59], v[58:59], 2, s[22:23]
	global_store_dword v[58:59], v82, off sc1
	v_lshl_or_b32 v58, v25, 10, v31
	v_ashrrev_i32_e32 v59, 31, v58
	v_lshl_add_u64 v[58:59], v[58:59], 2, s[22:23]
	global_store_dword v[58:59], v78, off sc1
	v_lshl_or_b32 v58, v24, 10, v31
	v_ashrrev_i32_e32 v59, 31, v58
	v_lshl_add_u64 v[58:59], v[58:59], 2, s[22:23]
	global_store_dword v[58:59], v74, off sc1
	v_lshl_or_b32 v58, v150, 10, v31
	v_ashrrev_i32_e32 v59, 31, v58
	v_lshl_add_u64 v[58:59], v[58:59], 2, s[22:23]
	global_store_dword v[58:59], v70, off sc1
	v_lshl_or_b32 v58, v152, 10, v31
	v_ashrrev_i32_e32 v59, 31, v58
	v_lshl_add_u64 v[58:59], v[58:59], 2, s[22:23]
	global_store_dword v[58:59], v72, off sc1
	v_lshl_or_b32 v58, v15, 10, v31
	v_ashrrev_i32_e32 v59, 31, v58
	v_lshl_add_u64 v[58:59], v[58:59], 2, s[22:23]
	global_store_dword v[58:59], v76, off sc1
	v_lshl_or_b32 v58, v14, 10, v31
	v_ashrrev_i32_e32 v59, 31, v58
	v_lshl_add_u64 v[58:59], v[58:59], 2, s[22:23]
	global_store_dword v[58:59], v68, off sc1
	v_lshl_or_b32 v58, v154, 10, v31
	v_ashrrev_i32_e32 v59, 31, v58
	v_lshl_add_u64 v[58:59], v[58:59], 2, s[22:23]
	global_store_dword v[58:59], v66, off sc1
	v_lshl_or_b32 v58, v80, 10, v31
	v_ashrrev_i32_e32 v59, 31, v58
	v_lshl_add_u64 v[58:59], v[58:59], 2, s[22:23]
	global_store_dword v[58:59], v64, off sc1
	v_lshl_or_b32 v58, v13, 10, v31
	v_ashrrev_i32_e32 v59, 31, v58
	v_lshl_add_u64 v[58:59], v[58:59], 2, s[22:23]
	global_store_dword v[58:59], v56, off sc1
	v_lshl_or_b32 v58, v12, 10, v31
	v_ashrrev_i32_e32 v59, 31, v58
	v_lshl_add_u64 v[58:59], v[58:59], 2, s[22:23]
	global_store_dword v[58:59], v54, off sc1
	v_lshl_or_b32 v58, v84, 10, v31
	v_ashrrev_i32_e32 v59, 31, v58
	v_lshl_add_u64 v[58:59], v[58:59], 2, s[22:23]
	global_store_dword v[58:59], v52, off sc1
	v_lshl_or_b32 v58, v88, 10, v31
	v_ashrrev_i32_e32 v59, 31, v58
	v_lshl_add_u64 v[58:59], v[58:59], 2, s[22:23]
	global_store_dword v[58:59], v50, off sc1
	v_lshl_or_b32 v58, v11, 10, v31
	v_ashrrev_i32_e32 v59, 31, v58
	v_lshl_add_u64 v[58:59], v[58:59], 2, s[22:23]
	global_store_dword v[58:59], v48, off sc1
	v_lshl_or_b32 v58, v10, 10, v31
	v_ashrrev_i32_e32 v59, 31, v58
	v_lshl_add_u64 v[58:59], v[58:59], 2, s[22:23]
	global_store_dword v[58:59], v46, off sc1
.LBB0_841:
	v_or_b32_e32 v58, s87, v164
	v_mul_lo_u32 v58, v58, s76
	v_or_b32_e32 v31, s75, v165
	v_add_u32_e32 v58, 0x800000, v58
	v_cndmask_b32_e64 v31, v31, v58, s[4:5]
	v_add_u32_e32 v58, v31, v27
	v_ashrrev_i32_e32 v59, 31, v58
	v_cvt_pk_bf16_f32 v60, v45, v43
	v_cvt_pk_bf16_f32 v61, v41, v39
	v_lshl_add_u64 v[58:59], v[58:59], 1, s[20:21]
	global_store_dwordx2 v[58:59], v[60:61], off sc1
	v_add_u32_e32 v58, v31, v28
	v_ashrrev_i32_e32 v59, 31, v58
	v_cvt_pk_bf16_f32 v60, v37, v35
	v_cvt_pk_bf16_f32 v61, v33, v23
	v_lshl_add_u64 v[58:59], v[58:59], 1, s[20:21]
	global_store_dwordx2 v[58:59], v[60:61], off sc1
	v_add_u32_e32 v58, v31, v29
	v_ashrrev_i32_e32 v59, 31, v58
	v_cvt_pk_bf16_f32 v60, v21, v19
	v_cvt_pk_bf16_f32 v61, v17, v9
	v_lshl_add_u64 v[58:59], v[58:59], 1, s[20:21]
	global_store_dwordx2 v[58:59], v[60:61], off sc1
	v_add_u32_e32 v58, v31, v30
	v_ashrrev_i32_e32 v59, 31, v58
	v_cvt_pk_bf16_f32 v60, v7, v5
	v_cvt_pk_bf16_f32 v61, v3, v1
	v_lshl_add_u64 v[58:59], v[58:59], 1, s[20:21]
	s_and_b64 vcc, exec, s[0:1]
	global_store_dwordx2 v[58:59], v[60:61], off sc1
	s_cbranch_vccnz .LBB0_843
	v_or_b32_e32 v31, s73, v164
	v_lshl_or_b32 v58, v148, 10, v31
	v_ashrrev_i32_e32 v59, 31, v58
	v_lshl_add_u64 v[58:59], v[58:59], 2, s[22:23]
	global_store_dword v[58:59], v45, off sc1
	v_lshl_or_b32 v58, v26, 10, v31
	v_ashrrev_i32_e32 v59, 31, v58
	v_lshl_add_u64 v[58:59], v[58:59], 2, s[22:23]
	global_store_dword v[58:59], v43, off sc1
	v_lshl_or_b32 v58, v25, 10, v31
	v_ashrrev_i32_e32 v59, 31, v58
	v_lshl_add_u64 v[58:59], v[58:59], 2, s[22:23]
	global_store_dword v[58:59], v41, off sc1
	v_lshl_or_b32 v58, v24, 10, v31
	v_ashrrev_i32_e32 v59, 31, v58
	v_lshl_add_u64 v[58:59], v[58:59], 2, s[22:23]
	global_store_dword v[58:59], v39, off sc1
	v_lshl_or_b32 v58, v150, 10, v31
	v_ashrrev_i32_e32 v59, 31, v58
	v_lshl_add_u64 v[58:59], v[58:59], 2, s[22:23]
	global_store_dword v[58:59], v37, off sc1
	v_lshl_or_b32 v58, v152, 10, v31
	v_ashrrev_i32_e32 v59, 31, v58
	v_lshl_add_u64 v[58:59], v[58:59], 2, s[22:23]
	global_store_dword v[58:59], v35, off sc1
	v_lshl_or_b32 v58, v15, 10, v31
	v_ashrrev_i32_e32 v59, 31, v58
	v_lshl_add_u64 v[58:59], v[58:59], 2, s[22:23]
	global_store_dword v[58:59], v33, off sc1
	v_lshl_or_b32 v58, v14, 10, v31
	v_ashrrev_i32_e32 v59, 31, v58
	v_lshl_add_u64 v[58:59], v[58:59], 2, s[22:23]
	global_store_dword v[58:59], v23, off sc1
	v_lshl_or_b32 v58, v154, 10, v31
	v_ashrrev_i32_e32 v59, 31, v58
	v_lshl_add_u64 v[58:59], v[58:59], 2, s[22:23]
	global_store_dword v[58:59], v21, off sc1
	v_lshl_or_b32 v58, v80, 10, v31
	v_ashrrev_i32_e32 v59, 31, v58
	v_lshl_add_u64 v[58:59], v[58:59], 2, s[22:23]
	global_store_dword v[58:59], v19, off sc1
	v_lshl_or_b32 v58, v13, 10, v31
	v_ashrrev_i32_e32 v59, 31, v58
	v_lshl_add_u64 v[58:59], v[58:59], 2, s[22:23]
	global_store_dword v[58:59], v17, off sc1
	v_lshl_or_b32 v58, v12, 10, v31
	v_ashrrev_i32_e32 v59, 31, v58
	v_lshl_add_u64 v[58:59], v[58:59], 2, s[22:23]
	global_store_dword v[58:59], v9, off sc1
	v_lshl_or_b32 v58, v84, 10, v31
	v_ashrrev_i32_e32 v59, 31, v58
	v_lshl_add_u64 v[58:59], v[58:59], 2, s[22:23]
	global_store_dword v[58:59], v7, off sc1
	v_lshl_or_b32 v58, v88, 10, v31
	v_ashrrev_i32_e32 v59, 31, v58
	v_lshl_add_u64 v[58:59], v[58:59], 2, s[22:23]
	global_store_dword v[58:59], v5, off sc1
	v_lshl_or_b32 v58, v11, 10, v31
	v_ashrrev_i32_e32 v59, 31, v58
	v_lshl_add_u64 v[58:59], v[58:59], 2, s[22:23]
	global_store_dword v[58:59], v3, off sc1
	v_lshl_or_b32 v58, v10, 10, v31
	v_ashrrev_i32_e32 v59, 31, v58
	v_lshl_add_u64 v[58:59], v[58:59], 2, s[22:23]
	global_store_dword v[58:59], v1, off sc1
.LBB0_843:
	v_or_b32_e32 v58, s87, v166
	v_mul_lo_u32 v58, v58, s76
	v_or_b32_e32 v31, s75, v167
	v_add_u32_e32 v58, 0x800000, v58
	v_cndmask_b32_e64 v31, v31, v58, s[4:5]
	v_add_u32_e32 v58, v31, v27
	v_ashrrev_i32_e32 v59, 31, v58
	v_cvt_pk_bf16_f32 v60, v44, v42
	v_cvt_pk_bf16_f32 v61, v40, v38
	v_lshl_add_u64 v[58:59], v[58:59], 1, s[20:21]
	global_store_dwordx2 v[58:59], v[60:61], off sc1
	v_add_u32_e32 v58, v31, v28
	v_ashrrev_i32_e32 v59, 31, v58
	v_add_u32_e32 v28, v31, v29
	v_cvt_pk_bf16_f32 v60, v36, v34
	v_cvt_pk_bf16_f32 v61, v32, v22
	v_lshl_add_u64 v[58:59], v[58:59], 1, s[20:21]
	v_ashrrev_i32_e32 v29, 31, v28
	global_store_dwordx2 v[58:59], v[60:61], off sc1
	v_cvt_pk_bf16_f32 v58, v20, v18
	v_cvt_pk_bf16_f32 v59, v16, v8
	v_lshl_add_u64 v[28:29], v[28:29], 1, s[20:21]
	global_store_dwordx2 v[28:29], v[58:59], off sc1
	v_add_u32_e32 v28, v31, v30
	v_ashrrev_i32_e32 v29, 31, v28
	v_cvt_pk_bf16_f32 v30, v6, v4
	v_cvt_pk_bf16_f32 v31, v2, v0
	v_lshl_add_u64 v[28:29], v[28:29], 1, s[20:21]
	s_and_b64 vcc, exec, s[0:1]
	global_store_dwordx2 v[28:29], v[30:31], off sc1
	s_cbranch_vccnz .LBB0_845
	v_or_b32_e32 v30, s73, v166
	v_lshl_or_b32 v26, v26, 10, v30
	v_ashrrev_i32_e32 v27, 31, v26
	v_lshl_add_u64 v[26:27], v[26:27], 2, s[22:23]
	v_lshl_or_b32 v24, v24, 10, v30
	global_store_dword v[26:27], v42, off sc1
	v_lshl_or_b32 v26, v25, 10, v30
	v_ashrrev_i32_e32 v25, 31, v24
	v_lshl_add_u64 v[24:25], v[24:25], 2, s[22:23]
	global_store_dword v[24:25], v38, off sc1
	v_lshl_or_b32 v24, v150, 10, v30
	v_ashrrev_i32_e32 v25, 31, v24
	v_lshl_add_u64 v[24:25], v[24:25], 2, s[22:23]
	global_store_dword v[24:25], v36, off sc1
	v_lshl_or_b32 v24, v152, 10, v30
	v_ashrrev_i32_e32 v25, 31, v24
	v_lshl_add_u64 v[24:25], v[24:25], 2, s[22:23]
	v_lshl_or_b32 v14, v14, 10, v30
	global_store_dword v[24:25], v34, off sc1
	v_lshl_or_b32 v24, v15, 10, v30
	v_ashrrev_i32_e32 v15, 31, v14
	v_lshl_add_u64 v[14:15], v[14:15], 2, s[22:23]
	global_store_dword v[14:15], v22, off sc1
	v_lshl_or_b32 v14, v154, 10, v30
	v_ashrrev_i32_e32 v15, 31, v14
	v_lshl_add_u64 v[14:15], v[14:15], 2, s[22:23]
	global_store_dword v[14:15], v20, off sc1
	v_lshl_or_b32 v14, v80, 10, v30
	v_ashrrev_i32_e32 v15, 31, v14
	v_lshl_add_u64 v[14:15], v[14:15], 2, s[22:23]
	v_lshl_or_b32 v12, v12, 10, v30
	global_store_dword v[14:15], v18, off sc1
	v_lshl_or_b32 v14, v13, 10, v30
	v_ashrrev_i32_e32 v13, 31, v12
	v_lshl_add_u64 v[12:13], v[12:13], 2, s[22:23]
	global_store_dword v[12:13], v8, off sc1
	v_lshl_or_b32 v12, v84, 10, v30
	v_ashrrev_i32_e32 v13, 31, v12
	v_lshl_add_u64 v[12:13], v[12:13], 2, s[22:23]
	global_store_dword v[12:13], v6, off sc1
	v_lshl_or_b32 v12, v88, 10, v30
	v_ashrrev_i32_e32 v13, 31, v12
	v_lshl_add_u64 v[12:13], v[12:13], 2, s[22:23]
	v_lshl_or_b32 v28, v148, 10, v30
	global_store_dword v[12:13], v4, off sc1
	v_lshl_or_b32 v12, v11, 10, v30
	v_lshl_or_b32 v10, v10, 10, v30
	v_ashrrev_i32_e32 v29, 31, v28
	v_ashrrev_i32_e32 v27, 31, v26
	v_ashrrev_i32_e32 v25, 31, v24
	v_ashrrev_i32_e32 v15, 31, v14
	v_ashrrev_i32_e32 v13, 31, v12
	v_ashrrev_i32_e32 v11, 31, v10
	v_lshl_add_u64 v[28:29], v[28:29], 2, s[22:23]
	v_lshl_add_u64 v[26:27], v[26:27], 2, s[22:23]
	v_lshl_add_u64 v[24:25], v[24:25], 2, s[22:23]
	v_lshl_add_u64 v[14:15], v[14:15], 2, s[22:23]
	v_lshl_add_u64 v[12:13], v[12:13], 2, s[22:23]
	v_lshl_add_u64 v[10:11], v[10:11], 2, s[22:23]
	global_store_dword v[28:29], v44, off sc1
	global_store_dword v[26:27], v40, off sc1
	global_store_dword v[24:25], v32, off sc1
	global_store_dword v[14:15], v16, off sc1
	global_store_dword v[12:13], v2, off sc1
	global_store_dword v[10:11], v0, off sc1

.LBB0_846:
	s_and_b64 vcc, exec, s[0:1]
	s_cbranch_vccz .LBB0_827
	v_mov_b32_e32 v10, s84
	ds_read_b64 v[10:11], v10
	s_lshl_b32 s0, s8, 6
	s_ashr_i32 s1, s0, 31
	s_lshl_b64 s[0:1], s[0:1], 2
	v_and_b32_e32 v15, 64, v204
	s_waitcnt lgkmcnt(0)
	v_readfirstlane_b32 s70, v10
	v_readfirstlane_b32 s71, v11
	s_add_u32 s0, s70, s0
	s_addc_u32 s1, s71, s1
	global_load_dword v11, v197, s[0:1]
	global_load_dword v10, v197, s[0:1] offset:128
	v_xor_b32_e32 v14, 1, v204
	v_add_u32_e32 v15, 64, v15
	v_pk_mul_f32 v[12:13], v[86:87], v[86:87]
	v_cmp_lt_i32_e32 vcc, v14, v15
	v_add_f32_e32 v12, v13, v12
	s_cmp_eq_u32 s8, 1
	v_cndmask_b32_e32 v13, v204, v14, vcc
	v_lshlrev_b32_e32 v100, 2, v13
	ds_bpermute_b32 v13, v100, v12
	v_xor_b32_e32 v14, 2, v204
	v_cmp_lt_i32_e32 vcc, v14, v15
	s_cselect_b64 s[0:1], -1, 0
	s_xor_b64 s[70:71], s[4:5], -1
	v_cndmask_b32_e32 v14, v204, v14, vcc
	v_lshlrev_b32_e32 v101, 2, v14
	s_waitcnt lgkmcnt(0)
	v_add_f32_e32 v12, v12, v13
	ds_bpermute_b32 v13, v101, v12
	v_xor_b32_e32 v14, 4, v204
	v_cmp_lt_i32_e32 vcc, v14, v15
	s_and_b64 s[70:71], s[70:71], s[0:1]
	v_lshl_or_b32 v134, s72, 7, v140
	v_cndmask_b32_e32 v14, v204, v14, vcc
	v_lshlrev_b32_e32 v102, 2, v14
	s_waitcnt lgkmcnt(0)
	v_add_f32_e32 v12, v12, v13
	ds_bpermute_b32 v13, v102, v12
	v_xor_b32_e32 v14, 8, v204
	v_cmp_lt_i32_e32 vcc, v14, v15
	s_waitcnt lgkmcnt(0)
	v_add_f32_e32 v12, v12, v13
	v_cndmask_b32_e32 v14, v204, v14, vcc
	v_lshlrev_b32_e32 v103, 2, v14
	ds_bpermute_b32 v13, v103, v12
	v_xor_b32_e32 v14, 16, v204
	v_cmp_lt_i32_e32 vcc, v14, v15
	s_waitcnt lgkmcnt(0)
	v_add_f32_e32 v12, v12, v13
	v_cndmask_b32_e32 v14, v204, v14, vcc
	v_lshlrev_b32_e32 v104, 2, v14
	ds_bpermute_b32 v13, v104, v12
	s_and_b64 vcc, exec, s[70:71]
	s_waitcnt lgkmcnt(0)
	v_add_f32_e32 v12, v12, v13
	v_fmamk_f32 v12, v12, 0x3c800000, v196
	v_rsq_f32_e32 v12, v12
	s_waitcnt vmcnt(0)
	v_pk_mul_f32 v[12:13], v[10:11], v[12:13] op_sel_hi:[1,0]
	s_nop 0
	v_pk_mul_f32 v[14:15], v[86:87], v[12:13]
	s_cbranch_vccz .LBB0_849
	v_lshl_or_b32 v12, v148, 10, v134
	v_ashrrev_i32_e32 v13, 31, v12
	v_lshl_add_u64 v[12:13], v[12:13], 2, s[26:27]
	global_store_dword v[12:13], v15, off sc1
	global_store_dword v[12:13], v14, off offset:128 sc1

.LBB0_851:
	v_pk_mul_f32 v[24:25], v[82:83], v[82:83]
	v_cvt_pk_bf16_f32 v28, v14, s0
	v_add_f32_e32 v13, v25, v24
	ds_bpermute_b32 v24, v100, v13
	s_cmp_lt_u32 s86, 8
	s_cselect_b64 s[4:5], -1, 0
	s_and_b64 s[4:5], s[4:5], exec
	s_cselect_b32 s8, s68, s74
	s_waitcnt lgkmcnt(0)
	v_add_f32_e32 v13, v13, v24
	ds_bpermute_b32 v24, v101, v13
	s_cselect_b32 s4, s85, 0xdf9f000
	s_add_u32 s4, s14, s4
	s_addc_u32 s5, s15, 0
	v_cvt_pk_bf16_f32 v25, v15, s0
	s_waitcnt lgkmcnt(0)
	v_add_f32_e32 v13, v13, v24
	ds_bpermute_b32 v24, v102, v13
	v_add_u32_e32 v15, s68, v168
	s_and_b64 vcc, exec, s[70:71]
	s_waitcnt lgkmcnt(0)
	v_add_f32_e32 v13, v13, v24
	ds_bpermute_b32 v14, v103, v13
	v_add_lshl_u32 v24, s8, v160, 10
	v_or_b32_e32 v26, v24, v134
	v_ashrrev_i32_e32 v27, 31, v26
	v_lshl_add_u64 v[26:27], v[26:27], 1, s[4:5]
	s_waitcnt lgkmcnt(0)
	v_add_f32_e32 v13, v13, v14
	ds_bpermute_b32 v14, v104, v13
	global_store_short v[26:27], v25, off sc1
	global_store_short v[26:27], v28, off offset:64 sc1
	s_waitcnt lgkmcnt(0)
	v_add_f32_e32 v13, v13, v14
	v_fmamk_f32 v13, v13, 0x3c800000, v196
	v_rsq_f32_e32 v14, v13
	s_nop 0
	v_pk_mul_f32 v[26:27], v[10:11], v[14:15] op_sel_hi:[1,0]
	s_nop 0
	v_pk_mul_f32 v[28:29], v[82:83], v[26:27]
	s_cbranch_vccz .LBB0_853
	v_lshl_or_b32 v26, v15, 10, v134
	v_ashrrev_i32_e32 v27, 31, v26
	v_lshl_add_u64 v[26:27], v[26:27], 2, s[26:27]
	global_store_dword v[26:27], v29, off sc1
	global_store_dword v[26:27], v28, off offset:128 sc1

.LBB0_855:
	v_pk_mul_f32 v[30:31], v[78:79], v[78:79]
	v_cvt_pk_bf16_f32 v58, v28, s0
	v_add_f32_e32 v13, v31, v30
	ds_bpermute_b32 v14, v100, v13
	v_cvt_pk_bf16_f32 v27, v29, s0
	v_add_u32_e32 v29, s68, v169
	s_and_b64 vcc, exec, s[70:71]
	s_waitcnt lgkmcnt(0)
	v_add_f32_e32 v13, v13, v14
	ds_bpermute_b32 v14, v101, v13
	s_waitcnt lgkmcnt(0)
	v_add_f32_e32 v13, v13, v14
	ds_bpermute_b32 v14, v102, v13
	s_waitcnt lgkmcnt(0)
	v_add_f32_e32 v13, v13, v14
	ds_bpermute_b32 v25, v103, v13
	v_add_lshl_u32 v14, s8, v168, 10
	v_or_b32_e32 v30, v14, v134
	v_ashrrev_i32_e32 v31, 31, v30
	v_lshl_add_u64 v[30:31], v[30:31], 1, s[4:5]
	s_waitcnt lgkmcnt(0)
	v_add_f32_e32 v13, v13, v25
	ds_bpermute_b32 v25, v104, v13
	global_store_short v[30:31], v27, off sc1
	global_store_short v[30:31], v58, off offset:64 sc1
	s_waitcnt lgkmcnt(0)
	v_add_f32_e32 v13, v13, v25
	v_fmamk_f32 v13, v13, 0x3c800000, v196
	v_rsq_f32_e32 v28, v13
	s_nop 0
	v_pk_mul_f32 v[30:31], v[10:11], v[28:29] op_sel_hi:[1,0]
	s_nop 0
	v_pk_mul_f32 v[58:59], v[78:79], v[30:31]
	s_cbranch_vccz .LBB0_857
	v_lshl_or_b32 v30, v29, 10, v134
	v_ashrrev_i32_e32 v31, 31, v30
	v_lshl_add_u64 v[30:31], v[30:31], 2, s[26:27]
	global_store_dword v[30:31], v59, off sc1
	global_store_dword v[30:31], v58, off offset:128 sc1

.LBB0_859:
	v_pk_mul_f32 v[60:61], v[74:75], v[74:75]
	v_add_lshl_u32 v28, s8, v169, 10
	v_add_f32_e32 v13, v61, v60
	ds_bpermute_b32 v25, v100, v13
	v_cvt_pk_bf16_f32 v31, v58, s0
	v_or_b32_e32 v60, v28, v134
	v_ashrrev_i32_e32 v61, 31, v60
	v_cvt_pk_bf16_f32 v27, v59, s0
	s_waitcnt lgkmcnt(0)
	v_add_f32_e32 v13, v13, v25
	ds_bpermute_b32 v25, v101, v13
	v_add_u32_e32 v59, s68, v170
	v_lshl_add_u64 v[60:61], v[60:61], 1, s[4:5]
	global_store_short v[60:61], v27, off sc1
	global_store_short v[60:61], v31, off offset:64 sc1
	s_and_b64 vcc, exec, s[70:71]
	s_waitcnt lgkmcnt(0)
	v_add_f32_e32 v13, v13, v25
	ds_bpermute_b32 v25, v102, v13
	s_waitcnt lgkmcnt(0)
	v_add_f32_e32 v13, v13, v25
	ds_bpermute_b32 v25, v103, v13
	s_waitcnt lgkmcnt(0)
	v_add_f32_e32 v13, v13, v25
	ds_bpermute_b32 v25, v104, v13
	s_waitcnt lgkmcnt(0)
	v_add_f32_e32 v13, v13, v25
	v_fmamk_f32 v13, v13, 0x3c800000, v196
	v_rsq_f32_e32 v58, v13
	s_nop 0
	v_pk_mul_f32 v[60:61], v[10:11], v[58:59] op_sel_hi:[1,0]
	s_nop 0
	v_pk_mul_f32 v[62:63], v[74:75], v[60:61]
	s_cbranch_vccz .LBB0_861
	v_lshl_or_b32 v60, v59, 10, v134
	v_ashrrev_i32_e32 v61, 31, v60
	v_lshl_add_u64 v[60:61], v[60:61], 2, s[26:27]
	global_store_dword v[60:61], v63, off sc1
	global_store_dword v[60:61], v62, off offset:128 sc1

.LBB0_863:
	v_pk_mul_f32 v[74:75], v[70:71], v[70:71]
	v_add_lshl_u32 v58, s8, v170, 10
	v_add_f32_e32 v13, v75, v74
	ds_bpermute_b32 v25, v100, v13
	v_cvt_pk_bf16_f32 v31, v62, s0
	v_or_b32_e32 v74, v58, v134
	v_ashrrev_i32_e32 v75, 31, v74
	v_cvt_pk_bf16_f32 v27, v63, s0
	s_waitcnt lgkmcnt(0)
	v_add_f32_e32 v13, v13, v25
	ds_bpermute_b32 v25, v101, v13
	v_add_u32_e32 v63, s68, v171
	v_lshl_add_u64 v[74:75], v[74:75], 1, s[4:5]
	global_store_short v[74:75], v27, off sc1
	global_store_short v[74:75], v31, off offset:64 sc1
	s_and_b64 vcc, exec, s[70:71]
	s_waitcnt lgkmcnt(0)
	v_add_f32_e32 v13, v13, v25
	ds_bpermute_b32 v25, v102, v13
	s_waitcnt lgkmcnt(0)
	v_add_f32_e32 v13, v13, v25
	ds_bpermute_b32 v25, v103, v13
	s_waitcnt lgkmcnt(0)
	v_add_f32_e32 v13, v13, v25
	ds_bpermute_b32 v25, v104, v13
	s_waitcnt lgkmcnt(0)
	v_add_f32_e32 v13, v13, v25
	v_fmamk_f32 v13, v13, 0x3c800000, v196
	v_rsq_f32_e32 v62, v13
	s_nop 0
	v_pk_mul_f32 v[74:75], v[10:11], v[62:63] op_sel_hi:[1,0]
	s_nop 0
	v_pk_mul_f32 v[74:75], v[70:71], v[74:75]
	s_cbranch_vccz .LBB0_865
	v_lshl_or_b32 v70, v63, 10, v134
	v_ashrrev_i32_e32 v71, 31, v70
	v_lshl_add_u64 v[70:71], v[70:71], 2, s[26:27]
	global_store_dword v[70:71], v75, off sc1
	global_store_dword v[70:71], v74, off offset:128 sc1

.LBB0_867:
	v_pk_mul_f32 v[78:79], v[72:73], v[72:73]
	v_add_lshl_u32 v62, s8, v171, 10
	v_add_f32_e32 v13, v79, v78
	ds_bpermute_b32 v25, v100, v13
	v_cvt_pk_bf16_f32 v31, v74, s0
	v_or_b32_e32 v74, v62, v134
	v_cvt_pk_bf16_f32 v27, v75, s0
	v_ashrrev_i32_e32 v75, 31, v74
	s_waitcnt lgkmcnt(0)
	v_add_f32_e32 v13, v13, v25
	ds_bpermute_b32 v25, v101, v13
	v_lshl_add_u64 v[74:75], v[74:75], 1, s[4:5]
	global_store_short v[74:75], v27, off sc1
	global_store_short v[74:75], v31, off offset:64 sc1
	s_and_b64 vcc, exec, s[70:71]
	v_add_u32_e32 v105, s68, v172
	s_waitcnt lgkmcnt(0)
	v_add_f32_e32 v13, v13, v25
	ds_bpermute_b32 v25, v102, v13
	s_waitcnt lgkmcnt(0)
	v_add_f32_e32 v13, v13, v25
	ds_bpermute_b32 v25, v103, v13
	s_waitcnt lgkmcnt(0)
	v_add_f32_e32 v13, v13, v25
	ds_bpermute_b32 v25, v104, v13
	s_waitcnt lgkmcnt(0)
	v_add_f32_e32 v13, v13, v25
	v_fmamk_f32 v13, v13, 0x3c800000, v196
	v_rsq_f32_e32 v78, v13
	s_nop 0
	v_pk_mul_f32 v[74:75], v[10:11], v[78:79] op_sel_hi:[1,0]
	s_nop 0
	v_pk_mul_f32 v[78:79], v[72:73], v[74:75]
	s_cbranch_vccz .LBB0_869
	v_lshl_or_b32 v72, v105, 10, v134
	v_ashrrev_i32_e32 v73, 31, v72
	v_lshl_add_u64 v[72:73], v[72:73], 2, s[26:27]
	global_store_dword v[72:73], v79, off sc1
	global_store_dword v[72:73], v78, off offset:128 sc1

.LBB0_871:
	v_pk_mul_f32 v[72:73], v[76:77], v[76:77]
	v_cvt_pk_bf16_f32 v31, v78, s0
	v_add_f32_e32 v13, v73, v72
	ds_bpermute_b32 v25, v100, v13
	v_add_lshl_u32 v72, s8, v172, 10
	v_or_b32_e32 v78, v72, v134
	v_cvt_pk_bf16_f32 v27, v79, s0
	v_ashrrev_i32_e32 v79, 31, v78
	s_waitcnt lgkmcnt(0)
	v_add_f32_e32 v13, v13, v25
	ds_bpermute_b32 v25, v101, v13
	v_lshl_add_u64 v[78:79], v[78:79], 1, s[4:5]
	global_store_short v[78:79], v27, off sc1
	global_store_short v[78:79], v31, off offset:64 sc1
	s_and_b64 vcc, exec, s[70:71]
	v_add_u32_e32 v106, s68, v173
	s_waitcnt lgkmcnt(0)
	v_add_f32_e32 v13, v13, v25
	ds_bpermute_b32 v25, v102, v13
	s_waitcnt lgkmcnt(0)
	v_add_f32_e32 v13, v13, v25
	ds_bpermute_b32 v25, v103, v13
	s_waitcnt lgkmcnt(0)
	v_add_f32_e32 v13, v13, v25
	ds_bpermute_b32 v25, v104, v13
	s_waitcnt lgkmcnt(0)
	v_add_f32_e32 v13, v13, v25
	v_fmamk_f32 v13, v13, 0x3c800000, v196
	v_rsq_f32_e32 v80, v13
	s_nop 0
	v_pk_mul_f32 v[78:79], v[10:11], v[80:81] op_sel_hi:[1,0]
	s_nop 0
	v_pk_mul_f32 v[80:81], v[76:77], v[78:79]
	s_cbranch_vccz .LBB0_873
	v_lshl_or_b32 v76, v106, 10, v134
	v_ashrrev_i32_e32 v77, 31, v76
	v_lshl_add_u64 v[76:77], v[76:77], 2, s[26:27]
	global_store_dword v[76:77], v81, off sc1
	global_store_dword v[76:77], v80, off offset:128 sc1

.LBB0_875:
	v_pk_mul_f32 v[76:77], v[68:69], v[68:69]
	v_cvt_pk_bf16_f32 v31, v80, s0
	v_add_f32_e32 v13, v77, v76
	ds_bpermute_b32 v25, v100, v13
	v_add_lshl_u32 v76, s8, v173, 10
	v_or_b32_e32 v80, v76, v134
	v_cvt_pk_bf16_f32 v27, v81, s0
	v_ashrrev_i32_e32 v81, 31, v80
	s_waitcnt lgkmcnt(0)
	v_add_f32_e32 v13, v13, v25
	ds_bpermute_b32 v25, v101, v13
	v_lshl_add_u64 v[80:81], v[80:81], 1, s[4:5]
	global_store_short v[80:81], v27, off sc1
	global_store_short v[80:81], v31, off offset:64 sc1
	s_and_b64 vcc, exec, s[70:71]
	v_add_u32_e32 v107, s68, v174
	s_waitcnt lgkmcnt(0)
	v_add_f32_e32 v13, v13, v25
	ds_bpermute_b32 v25, v102, v13
	s_waitcnt lgkmcnt(0)
	v_add_f32_e32 v13, v13, v25
	ds_bpermute_b32 v25, v103, v13
	s_waitcnt lgkmcnt(0)
	v_add_f32_e32 v13, v13, v25
	ds_bpermute_b32 v25, v104, v13
	s_waitcnt lgkmcnt(0)
	v_add_f32_e32 v13, v13, v25
	v_fmamk_f32 v13, v13, 0x3c800000, v196
	v_rsq_f32_e32 v82, v13
	s_nop 0
	v_pk_mul_f32 v[80:81], v[10:11], v[82:83] op_sel_hi:[1,0]
	s_nop 0
	v_pk_mul_f32 v[82:83], v[68:69], v[80:81]
	s_cbranch_vccz .LBB0_877
	v_lshl_or_b32 v68, v107, 10, v134
	v_ashrrev_i32_e32 v69, 31, v68
	v_lshl_add_u64 v[68:69], v[68:69], 2, s[26:27]
	global_store_dword v[68:69], v83, off sc1
	global_store_dword v[68:69], v82, off offset:128 sc1

.LBB0_879:
	v_pk_mul_f32 v[68:69], v[66:67], v[66:67]
	v_cvt_pk_bf16_f32 v31, v82, s0
	v_add_f32_e32 v13, v69, v68
	ds_bpermute_b32 v25, v100, v13
	v_add_lshl_u32 v68, s8, v174, 10
	v_or_b32_e32 v82, v68, v134
	v_cvt_pk_bf16_f32 v27, v83, s0
	v_ashrrev_i32_e32 v83, 31, v82
	s_waitcnt lgkmcnt(0)
	v_add_f32_e32 v13, v13, v25
	ds_bpermute_b32 v25, v101, v13
	v_lshl_add_u64 v[82:83], v[82:83], 1, s[4:5]
	global_store_short v[82:83], v27, off sc1
	global_store_short v[82:83], v31, off offset:64 sc1
	s_and_b64 vcc, exec, s[70:71]
	v_add_u32_e32 v108, s68, v175
	s_waitcnt lgkmcnt(0)
	v_add_f32_e32 v13, v13, v25
	ds_bpermute_b32 v25, v102, v13
	s_waitcnt lgkmcnt(0)
	v_add_f32_e32 v13, v13, v25
	ds_bpermute_b32 v25, v103, v13
	s_waitcnt lgkmcnt(0)
	v_add_f32_e32 v13, v13, v25
	ds_bpermute_b32 v25, v104, v13
	s_waitcnt lgkmcnt(0)
	v_add_f32_e32 v13, v13, v25
	v_fmamk_f32 v13, v13, 0x3c800000, v196
	v_rsq_f32_e32 v84, v13
	s_nop 0
	v_pk_mul_f32 v[82:83], v[10:11], v[84:85] op_sel_hi:[1,0]
	s_nop 0
	v_pk_mul_f32 v[84:85], v[66:67], v[82:83]
	s_cbranch_vccz .LBB0_881
	v_lshl_or_b32 v66, v108, 10, v134
	v_ashrrev_i32_e32 v67, 31, v66
	v_lshl_add_u64 v[66:67], v[66:67], 2, s[26:27]
	global_store_dword v[66:67], v85, off sc1
	global_store_dword v[66:67], v84, off offset:128 sc1

.LBB0_883:
	v_pk_mul_f32 v[66:67], v[64:65], v[64:65]
	v_cvt_pk_bf16_f32 v31, v84, s0
	v_add_f32_e32 v13, v67, v66
	ds_bpermute_b32 v25, v100, v13
	v_add_lshl_u32 v66, s8, v175, 10
	v_or_b32_e32 v84, v66, v134
	v_cvt_pk_bf16_f32 v27, v85, s0
	v_ashrrev_i32_e32 v85, 31, v84
	s_waitcnt lgkmcnt(0)
	v_add_f32_e32 v13, v13, v25
	ds_bpermute_b32 v25, v101, v13
	v_lshl_add_u64 v[84:85], v[84:85], 1, s[4:5]
	global_store_short v[84:85], v27, off sc1
	global_store_short v[84:85], v31, off offset:64 sc1
	s_and_b64 vcc, exec, s[70:71]
	v_add_u32_e32 v109, s68, v176
	s_waitcnt lgkmcnt(0)
	v_add_f32_e32 v13, v13, v25
	ds_bpermute_b32 v25, v102, v13
	s_waitcnt lgkmcnt(0)
	v_add_f32_e32 v13, v13, v25
	ds_bpermute_b32 v25, v103, v13
	s_waitcnt lgkmcnt(0)
	v_add_f32_e32 v13, v13, v25
	ds_bpermute_b32 v25, v104, v13
	s_waitcnt lgkmcnt(0)
	v_add_f32_e32 v13, v13, v25
	v_fmamk_f32 v13, v13, 0x3c800000, v196
	v_rsq_f32_e32 v86, v13
	s_nop 0
	v_pk_mul_f32 v[84:85], v[10:11], v[86:87] op_sel_hi:[1,0]
	s_nop 0
	v_pk_mul_f32 v[86:87], v[64:65], v[84:85]
	s_cbranch_vccz .LBB0_885
	v_lshl_or_b32 v64, v109, 10, v134
	v_ashrrev_i32_e32 v65, 31, v64
	v_lshl_add_u64 v[64:65], v[64:65], 2, s[26:27]
	global_store_dword v[64:65], v87, off sc1
	global_store_dword v[64:65], v86, off offset:128 sc1

.LBB0_887:
	v_pk_mul_f32 v[64:65], v[56:57], v[56:57]
	v_cvt_pk_bf16_f32 v31, v86, s0
	v_add_f32_e32 v13, v65, v64
	ds_bpermute_b32 v25, v100, v13
	v_add_lshl_u32 v64, s8, v176, 10
	v_or_b32_e32 v86, v64, v134
	v_cvt_pk_bf16_f32 v27, v87, s0
	v_ashrrev_i32_e32 v87, 31, v86
	s_waitcnt lgkmcnt(0)
	v_add_f32_e32 v13, v13, v25
	ds_bpermute_b32 v25, v101, v13
	v_lshl_add_u64 v[86:87], v[86:87], 1, s[4:5]
	global_store_short v[86:87], v27, off sc1
	global_store_short v[86:87], v31, off offset:64 sc1
	s_and_b64 vcc, exec, s[70:71]
	v_add_u32_e32 v110, s68, v177
	s_waitcnt lgkmcnt(0)
	v_add_f32_e32 v13, v13, v25
	ds_bpermute_b32 v25, v102, v13
	s_waitcnt lgkmcnt(0)
	v_add_f32_e32 v13, v13, v25
	ds_bpermute_b32 v25, v103, v13
	s_waitcnt lgkmcnt(0)
	v_add_f32_e32 v13, v13, v25
	ds_bpermute_b32 v25, v104, v13
	s_waitcnt lgkmcnt(0)
	v_add_f32_e32 v13, v13, v25
	v_fmamk_f32 v13, v13, 0x3c800000, v196
	v_rsq_f32_e32 v88, v13
	s_nop 0
	v_pk_mul_f32 v[86:87], v[10:11], v[88:89] op_sel_hi:[1,0]
	s_nop 0
	v_pk_mul_f32 v[88:89], v[56:57], v[86:87]
	s_cbranch_vccz .LBB0_889
	v_lshl_or_b32 v56, v110, 10, v134
	v_ashrrev_i32_e32 v57, 31, v56
	v_lshl_add_u64 v[56:57], v[56:57], 2, s[26:27]
	global_store_dword v[56:57], v89, off sc1
	global_store_dword v[56:57], v88, off offset:128 sc1

.LBB0_891:
	v_pk_mul_f32 v[56:57], v[54:55], v[54:55]
	v_cvt_pk_bf16_f32 v31, v88, s0
	v_add_f32_e32 v13, v57, v56
	ds_bpermute_b32 v25, v100, v13
	v_add_lshl_u32 v56, s8, v177, 10
	v_or_b32_e32 v88, v56, v134
	v_cvt_pk_bf16_f32 v27, v89, s0
	v_ashrrev_i32_e32 v89, 31, v88
	s_waitcnt lgkmcnt(0)
	v_add_f32_e32 v13, v13, v25
	ds_bpermute_b32 v25, v101, v13
	v_lshl_add_u64 v[88:89], v[88:89], 1, s[4:5]
	global_store_short v[88:89], v27, off sc1
	global_store_short v[88:89], v31, off offset:64 sc1
	s_and_b64 vcc, exec, s[70:71]
	v_add_u32_e32 v111, s68, v178
	s_waitcnt lgkmcnt(0)
	v_add_f32_e32 v13, v13, v25
	ds_bpermute_b32 v25, v102, v13
	s_waitcnt lgkmcnt(0)
	v_add_f32_e32 v13, v13, v25
	ds_bpermute_b32 v25, v103, v13
	s_waitcnt lgkmcnt(0)
	v_add_f32_e32 v13, v13, v25
	ds_bpermute_b32 v25, v104, v13
	s_waitcnt lgkmcnt(0)
	v_add_f32_e32 v13, v13, v25
	v_fmamk_f32 v13, v13, 0x3c800000, v196
	v_rsq_f32_e32 v90, v13
	s_nop 0
	v_pk_mul_f32 v[88:89], v[10:11], v[90:91] op_sel_hi:[1,0]
	s_nop 0
	v_pk_mul_f32 v[90:91], v[54:55], v[88:89]
	s_cbranch_vccz .LBB0_893
	v_lshl_or_b32 v54, v111, 10, v134
	v_ashrrev_i32_e32 v55, 31, v54
	v_lshl_add_u64 v[54:55], v[54:55], 2, s[26:27]
	global_store_dword v[54:55], v91, off sc1
	global_store_dword v[54:55], v90, off offset:128 sc1

.LBB0_895:
	v_pk_mul_f32 v[54:55], v[52:53], v[52:53]
	v_cvt_pk_bf16_f32 v31, v90, s0
	v_add_f32_e32 v13, v55, v54
	ds_bpermute_b32 v25, v100, v13
	v_add_lshl_u32 v54, s8, v178, 10
	v_or_b32_e32 v90, v54, v134
	v_cvt_pk_bf16_f32 v27, v91, s0
	v_ashrrev_i32_e32 v91, 31, v90
	s_waitcnt lgkmcnt(0)
	v_add_f32_e32 v13, v13, v25
	ds_bpermute_b32 v25, v101, v13
	v_lshl_add_u64 v[90:91], v[90:91], 1, s[4:5]
	global_store_short v[90:91], v27, off sc1
	global_store_short v[90:91], v31, off offset:64 sc1
	s_and_b64 vcc, exec, s[70:71]
	v_add_u32_e32 v112, s68, v179
	s_waitcnt lgkmcnt(0)
	v_add_f32_e32 v13, v13, v25
	ds_bpermute_b32 v25, v102, v13
	s_waitcnt lgkmcnt(0)
	v_add_f32_e32 v13, v13, v25
	ds_bpermute_b32 v25, v103, v13
	s_waitcnt lgkmcnt(0)
	v_add_f32_e32 v13, v13, v25
	ds_bpermute_b32 v25, v104, v13
	s_waitcnt lgkmcnt(0)
	v_add_f32_e32 v13, v13, v25
	v_fmamk_f32 v13, v13, 0x3c800000, v196
	v_rsq_f32_e32 v92, v13
	s_nop 0
	v_pk_mul_f32 v[90:91], v[10:11], v[92:93] op_sel_hi:[1,0]
	s_nop 0
	v_pk_mul_f32 v[92:93], v[52:53], v[90:91]
	s_cbranch_vccz .LBB0_897
	v_lshl_or_b32 v52, v112, 10, v134
	v_ashrrev_i32_e32 v53, 31, v52
	v_lshl_add_u64 v[52:53], v[52:53], 2, s[26:27]
	global_store_dword v[52:53], v93, off sc1
	global_store_dword v[52:53], v92, off offset:128 sc1

.LBB0_899:
	v_pk_mul_f32 v[52:53], v[50:51], v[50:51]
	v_cvt_pk_bf16_f32 v31, v92, s0
	v_add_f32_e32 v13, v53, v52
	ds_bpermute_b32 v25, v100, v13
	v_add_lshl_u32 v52, s8, v179, 10
	v_or_b32_e32 v92, v52, v134
	v_cvt_pk_bf16_f32 v27, v93, s0
	v_ashrrev_i32_e32 v93, 31, v92
	s_waitcnt lgkmcnt(0)
	v_add_f32_e32 v13, v13, v25
	ds_bpermute_b32 v25, v101, v13
	v_lshl_add_u64 v[92:93], v[92:93], 1, s[4:5]
	global_store_short v[92:93], v27, off sc1
	global_store_short v[92:93], v31, off offset:64 sc1
	s_and_b64 vcc, exec, s[70:71]
	v_add_u32_e32 v113, s68, v180
	s_waitcnt lgkmcnt(0)
	v_add_f32_e32 v13, v13, v25
	ds_bpermute_b32 v25, v102, v13
	s_waitcnt lgkmcnt(0)
	v_add_f32_e32 v13, v13, v25
	ds_bpermute_b32 v25, v103, v13
	s_waitcnt lgkmcnt(0)
	v_add_f32_e32 v13, v13, v25
	ds_bpermute_b32 v25, v104, v13
	s_waitcnt lgkmcnt(0)
	v_add_f32_e32 v13, v13, v25
	v_fmamk_f32 v13, v13, 0x3c800000, v196
	v_rsq_f32_e32 v94, v13
	s_nop 0
	v_pk_mul_f32 v[92:93], v[10:11], v[94:95] op_sel_hi:[1,0]
	s_nop 0
	v_pk_mul_f32 v[94:95], v[50:51], v[92:93]
	s_cbranch_vccz .LBB0_901
	v_lshl_or_b32 v50, v113, 10, v134
	v_ashrrev_i32_e32 v51, 31, v50
	v_lshl_add_u64 v[50:51], v[50:51], 2, s[26:27]
	global_store_dword v[50:51], v95, off sc1
	global_store_dword v[50:51], v94, off offset:128 sc1

.LBB0_903:
	v_pk_mul_f32 v[50:51], v[48:49], v[48:49]
	v_cvt_pk_bf16_f32 v31, v94, s0
	v_add_f32_e32 v13, v51, v50
	ds_bpermute_b32 v25, v100, v13
	v_add_lshl_u32 v50, s8, v180, 10
	v_or_b32_e32 v94, v50, v134
	v_cvt_pk_bf16_f32 v27, v95, s0
	v_ashrrev_i32_e32 v95, 31, v94
	s_waitcnt lgkmcnt(0)
	v_add_f32_e32 v13, v13, v25
	ds_bpermute_b32 v25, v101, v13
	v_lshl_add_u64 v[94:95], v[94:95], 1, s[4:5]
	global_store_short v[94:95], v27, off sc1
	global_store_short v[94:95], v31, off offset:64 sc1
	s_and_b64 vcc, exec, s[70:71]
	v_add_u32_e32 v114, s68, v181
	s_waitcnt lgkmcnt(0)
	v_add_f32_e32 v13, v13, v25
	ds_bpermute_b32 v25, v102, v13
	s_waitcnt lgkmcnt(0)
	v_add_f32_e32 v13, v13, v25
	ds_bpermute_b32 v25, v103, v13
	s_waitcnt lgkmcnt(0)
	v_add_f32_e32 v13, v13, v25
	ds_bpermute_b32 v25, v104, v13
	s_waitcnt lgkmcnt(0)
	v_add_f32_e32 v13, v13, v25
	v_fmamk_f32 v13, v13, 0x3c800000, v196
	v_rsq_f32_e32 v96, v13
	s_nop 0
	v_pk_mul_f32 v[94:95], v[10:11], v[96:97] op_sel_hi:[1,0]
	s_nop 0
	v_pk_mul_f32 v[96:97], v[48:49], v[94:95]
	s_cbranch_vccz .LBB0_905
	v_lshl_or_b32 v48, v114, 10, v134
	v_ashrrev_i32_e32 v49, 31, v48
	v_lshl_add_u64 v[48:49], v[48:49], 2, s[26:27]
	global_store_dword v[48:49], v97, off sc1
	global_store_dword v[48:49], v96, off offset:128 sc1

.LBB0_907:
	v_pk_mul_f32 v[48:49], v[46:47], v[46:47]
	v_cvt_pk_bf16_f32 v31, v96, s0
	v_add_f32_e32 v13, v49, v48
	ds_bpermute_b32 v25, v100, v13
	v_add_lshl_u32 v48, s8, v181, 10
	v_or_b32_e32 v98, v48, v134
	v_ashrrev_i32_e32 v99, 31, v98
	v_cvt_pk_bf16_f32 v27, v97, s0
	s_waitcnt lgkmcnt(0)
	v_add_f32_e32 v13, v13, v25
	ds_bpermute_b32 v25, v101, v13
	v_add_u32_e32 v97, s68, v182
	v_lshl_add_u64 v[98:99], v[98:99], 1, s[4:5]
	global_store_short v[98:99], v27, off sc1
	global_store_short v[98:99], v31, off offset:64 sc1
	s_and_b64 vcc, exec, s[70:71]
	s_waitcnt lgkmcnt(0)
	v_add_f32_e32 v13, v13, v25
	ds_bpermute_b32 v25, v102, v13
	s_waitcnt lgkmcnt(0)
	v_add_f32_e32 v13, v13, v25
	ds_bpermute_b32 v25, v103, v13
	s_waitcnt lgkmcnt(0)
	v_add_f32_e32 v13, v13, v25
	ds_bpermute_b32 v25, v104, v13
	s_waitcnt lgkmcnt(0)
	v_add_f32_e32 v13, v13, v25
	v_fmamk_f32 v13, v13, 0x3c800000, v196
	v_rsq_f32_e32 v96, v13
	s_nop 0
	v_pk_mul_f32 v[98:99], v[10:11], v[96:97] op_sel_hi:[1,0]
	s_nop 0
	v_pk_mul_f32 v[98:99], v[46:47], v[98:99]
	s_cbranch_vccz .LBB0_909
	v_lshl_or_b32 v46, v97, 10, v134
	v_ashrrev_i32_e32 v47, 31, v46
	v_lshl_add_u64 v[46:47], v[46:47], 2, s[26:27]
	global_store_dword v[46:47], v99, off sc1
	global_store_dword v[46:47], v98, off offset:128 sc1

.LBB0_911:
	v_pk_mul_f32 v[116:117], v[44:45], v[44:45]
	v_add_lshl_u32 v96, s8, v182, 10
	v_add_f32_e32 v13, v117, v116
	ds_bpermute_b32 v25, v100, v13
	v_cvt_pk_bf16_f32 v31, v98, s0
	v_or_b32_e32 v98, v96, v134
	v_cvt_pk_bf16_f32 v27, v99, s0
	v_ashrrev_i32_e32 v99, 31, v98
	s_waitcnt lgkmcnt(0)
	v_add_f32_e32 v13, v13, v25
	ds_bpermute_b32 v25, v101, v13
	v_lshl_add_u64 v[98:99], v[98:99], 1, s[4:5]
	global_store_short v[98:99], v27, off sc1
	global_store_short v[98:99], v31, off offset:64 sc1
	v_or_b32_e32 v47, 64, v134
	s_and_b64 vcc, exec, s[70:71]
	s_waitcnt lgkmcnt(0)
	v_add_f32_e32 v13, v13, v25
	ds_bpermute_b32 v25, v102, v13
	s_waitcnt lgkmcnt(0)
	v_add_f32_e32 v13, v13, v25
	ds_bpermute_b32 v25, v103, v13
	s_waitcnt lgkmcnt(0)
	v_add_f32_e32 v13, v13, v25
	ds_bpermute_b32 v25, v104, v13
	s_waitcnt lgkmcnt(0)
	v_add_f32_e32 v13, v13, v25
	v_fmamk_f32 v13, v13, 0x3c800000, v196
	v_rsq_f32_e32 v116, v13
	s_nop 0
	v_pk_mul_f32 v[98:99], v[10:11], v[116:117] op_sel_hi:[1,0]
	s_nop 0
	v_pk_mul_f32 v[44:45], v[44:45], v[98:99]
	s_cbranch_vccz .LBB0_913
	v_lshl_or_b32 v98, v148, 10, v47
	v_ashrrev_i32_e32 v99, 31, v98
	v_lshl_add_u64 v[98:99], v[98:99], 2, s[26:27]
	global_store_dword v[98:99], v45, off sc1
	global_store_dword v[98:99], v44, off offset:128 sc1

.LBB0_915:
	v_pk_mul_f32 v[12:13], v[42:43], v[42:43]
	v_cvt_pk_bf16_f32 v27, v45, s0
	v_add_f32_e32 v12, v13, v12
	ds_bpermute_b32 v13, v100, v12
	v_ashrrev_i32_e32 v25, 31, v24
	v_cvt_pk_bf16_f32 v44, v44, s0
	s_and_b64 vcc, exec, s[70:71]
	s_waitcnt lgkmcnt(0)
	v_add_f32_e32 v12, v12, v13
	ds_bpermute_b32 v13, v101, v12
	s_waitcnt lgkmcnt(0)
	v_add_f32_e32 v12, v12, v13
	ds_bpermute_b32 v13, v102, v12
	s_waitcnt lgkmcnt(0)
	v_add_f32_e32 v12, v12, v13
	ds_bpermute_b32 v13, v103, v12
	s_waitcnt lgkmcnt(0)
	v_add_f32_e32 v31, v12, v13
	ds_bpermute_b32 v45, v104, v31
	v_lshl_add_u64 v[12:13], v[24:25], 0, v[134:135]
	v_lshl_add_u64 v[12:13], v[12:13], 1, s[4:5]
	global_store_short v[12:13], v27, off offset:128 sc1
	global_store_short v[12:13], v44, off offset:192 sc1
	s_waitcnt lgkmcnt(0)
	v_add_f32_e32 v24, v31, v45
	v_fmamk_f32 v24, v24, 0x3c800000, v196
	v_rsq_f32_e32 v24, v24
	s_nop 0
	v_pk_mul_f32 v[12:13], v[10:11], v[24:25] op_sel_hi:[1,0]
	s_nop 0
	v_pk_mul_f32 v[12:13], v[42:43], v[12:13]
	s_cbranch_vccz .LBB0_917
	v_lshl_or_b32 v24, v15, 10, v47
	v_ashrrev_i32_e32 v25, 31, v24
	v_lshl_add_u64 v[24:25], v[24:25], 2, s[26:27]
	global_store_dword v[24:25], v13, off sc1
	global_store_dword v[24:25], v12, off offset:128 sc1

.LBB0_919:
	v_pk_mul_f32 v[24:25], v[40:41], v[40:41]
	v_cvt_pk_bf16_f32 v27, v12, s0
	v_add_f32_e32 v15, v25, v24
	ds_bpermute_b32 v24, v100, v15
	v_cvt_pk_bf16_f32 v25, v13, s0
	s_and_b64 vcc, exec, s[70:71]
	s_waitcnt lgkmcnt(0)
	v_add_f32_e32 v15, v15, v24
	ds_bpermute_b32 v24, v101, v15
	s_waitcnt lgkmcnt(0)
	v_add_f32_e32 v15, v15, v24
	ds_bpermute_b32 v24, v102, v15
	s_waitcnt lgkmcnt(0)
	v_add_f32_e32 v15, v15, v24
	ds_bpermute_b32 v24, v103, v15
	s_waitcnt lgkmcnt(0)
	v_add_f32_e32 v24, v15, v24
	ds_bpermute_b32 v26, v104, v24
	v_ashrrev_i32_e32 v15, 31, v14
	v_lshl_add_u64 v[12:13], v[14:15], 0, v[134:135]
	v_lshl_add_u64 v[12:13], v[12:13], 1, s[4:5]
	global_store_short v[12:13], v25, off offset:128 sc1
	global_store_short v[12:13], v27, off offset:192 sc1
	s_waitcnt lgkmcnt(0)
	v_add_f32_e32 v14, v24, v26
	v_fmamk_f32 v14, v14, 0x3c800000, v196
	v_rsq_f32_e32 v14, v14
	s_nop 0
	v_pk_mul_f32 v[12:13], v[10:11], v[14:15] op_sel_hi:[1,0]
	s_nop 0
	v_pk_mul_f32 v[12:13], v[40:41], v[12:13]
	s_cbranch_vccz .LBB0_921
	v_lshl_or_b32 v14, v29, 10, v47
	v_ashrrev_i32_e32 v15, 31, v14
	v_lshl_add_u64 v[14:15], v[14:15], 2, s[26:27]
	global_store_dword v[14:15], v13, off sc1
	global_store_dword v[14:15], v12, off offset:128 sc1

.LBB0_923:
	v_pk_mul_f32 v[14:15], v[38:39], v[38:39]
	v_ashrrev_i32_e32 v29, 31, v28
	v_add_f32_e32 v14, v15, v14
	ds_bpermute_b32 v15, v100, v14
	v_cvt_pk_bf16_f32 v24, v13, s0
	v_cvt_pk_bf16_f32 v25, v12, s0
	v_lshl_add_u64 v[12:13], v[28:29], 0, v[134:135]
	v_lshl_add_u64 v[12:13], v[12:13], 1, s[4:5]
	s_waitcnt lgkmcnt(0)
	v_add_f32_e32 v14, v14, v15
	ds_bpermute_b32 v15, v101, v14
	global_store_short v[12:13], v24, off offset:128 sc1
	global_store_short v[12:13], v25, off offset:192 sc1
	s_and_b64 vcc, exec, s[70:71]
	s_waitcnt lgkmcnt(0)
	v_add_f32_e32 v14, v14, v15
	ds_bpermute_b32 v15, v102, v14
	s_waitcnt lgkmcnt(0)
	v_add_f32_e32 v14, v14, v15
	ds_bpermute_b32 v15, v103, v14
	s_waitcnt lgkmcnt(0)
	v_add_f32_e32 v14, v14, v15
	ds_bpermute_b32 v15, v104, v14
	s_waitcnt lgkmcnt(0)
	v_add_f32_e32 v14, v14, v15
	v_fmamk_f32 v14, v14, 0x3c800000, v196
	v_rsq_f32_e32 v14, v14
	s_nop 0
	v_pk_mul_f32 v[12:13], v[10:11], v[14:15] op_sel_hi:[1,0]
	s_nop 0
	v_pk_mul_f32 v[12:13], v[38:39], v[12:13]
	s_cbranch_vccz .LBB0_925
	v_lshl_or_b32 v14, v59, 10, v47
	v_ashrrev_i32_e32 v15, 31, v14
	v_lshl_add_u64 v[14:15], v[14:15], 2, s[26:27]
	global_store_dword v[14:15], v13, off sc1
	global_store_dword v[14:15], v12, off offset:128 sc1

.LBB0_927:
	v_pk_mul_f32 v[14:15], v[36:37], v[36:37]
	v_ashrrev_i32_e32 v59, 31, v58
	v_add_f32_e32 v14, v15, v14
	ds_bpermute_b32 v15, v100, v14
	v_cvt_pk_bf16_f32 v24, v13, s0
	v_cvt_pk_bf16_f32 v25, v12, s0
	v_lshl_add_u64 v[12:13], v[58:59], 0, v[134:135]
	v_lshl_add_u64 v[12:13], v[12:13], 1, s[4:5]
	s_waitcnt lgkmcnt(0)
	v_add_f32_e32 v14, v14, v15
	ds_bpermute_b32 v15, v101, v14
	global_store_short v[12:13], v24, off offset:128 sc1
	global_store_short v[12:13], v25, off offset:192 sc1
	s_and_b64 vcc, exec, s[70:71]
	s_waitcnt lgkmcnt(0)
	v_add_f32_e32 v14, v14, v15
	ds_bpermute_b32 v15, v102, v14
	s_waitcnt lgkmcnt(0)
	v_add_f32_e32 v14, v14, v15
	ds_bpermute_b32 v15, v103, v14
	s_waitcnt lgkmcnt(0)
	v_add_f32_e32 v14, v14, v15
	ds_bpermute_b32 v15, v104, v14
	s_waitcnt lgkmcnt(0)
	v_add_f32_e32 v14, v14, v15
	v_fmamk_f32 v14, v14, 0x3c800000, v196
	v_rsq_f32_e32 v14, v14
	s_nop 0
	v_pk_mul_f32 v[12:13], v[10:11], v[14:15] op_sel_hi:[1,0]
	s_nop 0
	v_pk_mul_f32 v[12:13], v[36:37], v[12:13]
	s_cbranch_vccz .LBB0_929
	v_lshl_or_b32 v14, v63, 10, v47
	v_ashrrev_i32_e32 v15, 31, v14
	v_lshl_add_u64 v[14:15], v[14:15], 2, s[26:27]
	global_store_dword v[14:15], v13, off sc1
	global_store_dword v[14:15], v12, off offset:128 sc1

.LBB0_931:
	v_pk_mul_f32 v[14:15], v[34:35], v[34:35]
	v_ashrrev_i32_e32 v63, 31, v62
	v_add_f32_e32 v14, v15, v14
	ds_bpermute_b32 v15, v100, v14
	v_cvt_pk_bf16_f32 v24, v13, s0
	v_cvt_pk_bf16_f32 v25, v12, s0
	v_lshl_add_u64 v[12:13], v[62:63], 0, v[134:135]
	v_lshl_add_u64 v[12:13], v[12:13], 1, s[4:5]
	s_waitcnt lgkmcnt(0)
	v_add_f32_e32 v14, v14, v15
	ds_bpermute_b32 v15, v101, v14
	global_store_short v[12:13], v24, off offset:128 sc1
	global_store_short v[12:13], v25, off offset:192 sc1
	s_and_b64 vcc, exec, s[70:71]
	s_waitcnt lgkmcnt(0)
	v_add_f32_e32 v14, v14, v15
	ds_bpermute_b32 v15, v102, v14
	s_waitcnt lgkmcnt(0)
	v_add_f32_e32 v14, v14, v15
	ds_bpermute_b32 v15, v103, v14
	s_waitcnt lgkmcnt(0)
	v_add_f32_e32 v14, v14, v15
	ds_bpermute_b32 v15, v104, v14
	s_waitcnt lgkmcnt(0)
	v_add_f32_e32 v14, v14, v15
	v_fmamk_f32 v14, v14, 0x3c800000, v196
	v_rsq_f32_e32 v14, v14
	s_nop 0
	v_pk_mul_f32 v[12:13], v[10:11], v[14:15] op_sel_hi:[1,0]
	s_nop 0
	v_pk_mul_f32 v[12:13], v[34:35], v[12:13]
	s_cbranch_vccz .LBB0_933
	v_lshl_or_b32 v14, v105, 10, v47
	v_ashrrev_i32_e32 v15, 31, v14
	v_lshl_add_u64 v[14:15], v[14:15], 2, s[26:27]
	global_store_dword v[14:15], v13, off sc1
	global_store_dword v[14:15], v12, off offset:128 sc1

.LBB0_935:
	v_pk_mul_f32 v[14:15], v[32:33], v[32:33]
	v_ashrrev_i32_e32 v73, 31, v72
	v_add_f32_e32 v14, v15, v14
	ds_bpermute_b32 v15, v100, v14
	v_cvt_pk_bf16_f32 v24, v13, s0
	v_cvt_pk_bf16_f32 v25, v12, s0
	v_lshl_add_u64 v[12:13], v[72:73], 0, v[134:135]
	v_lshl_add_u64 v[12:13], v[12:13], 1, s[4:5]
	s_waitcnt lgkmcnt(0)
	v_add_f32_e32 v14, v14, v15
	ds_bpermute_b32 v15, v101, v14
	global_store_short v[12:13], v24, off offset:128 sc1
	global_store_short v[12:13], v25, off offset:192 sc1
	s_and_b64 vcc, exec, s[70:71]
	s_waitcnt lgkmcnt(0)
	v_add_f32_e32 v14, v14, v15
	ds_bpermute_b32 v15, v102, v14
	s_waitcnt lgkmcnt(0)
	v_add_f32_e32 v14, v14, v15
	ds_bpermute_b32 v15, v103, v14
	s_waitcnt lgkmcnt(0)
	v_add_f32_e32 v14, v14, v15
	ds_bpermute_b32 v15, v104, v14
	s_waitcnt lgkmcnt(0)
	v_add_f32_e32 v14, v14, v15
	v_fmamk_f32 v14, v14, 0x3c800000, v196
	v_rsq_f32_e32 v14, v14
	s_nop 0
	v_pk_mul_f32 v[12:13], v[10:11], v[14:15] op_sel_hi:[1,0]
	s_nop 0
	v_pk_mul_f32 v[12:13], v[32:33], v[12:13]
	s_cbranch_vccz .LBB0_937
	v_lshl_or_b32 v14, v106, 10, v47
	v_ashrrev_i32_e32 v15, 31, v14
	v_lshl_add_u64 v[14:15], v[14:15], 2, s[26:27]
	global_store_dword v[14:15], v13, off sc1
	global_store_dword v[14:15], v12, off offset:128 sc1

.LBB0_939:
	v_pk_mul_f32 v[14:15], v[22:23], v[22:23]
	v_ashrrev_i32_e32 v77, 31, v76
	v_add_f32_e32 v14, v15, v14
	ds_bpermute_b32 v15, v100, v14
	v_cvt_pk_bf16_f32 v24, v13, s0
	v_cvt_pk_bf16_f32 v25, v12, s0
	v_lshl_add_u64 v[12:13], v[76:77], 0, v[134:135]
	v_lshl_add_u64 v[12:13], v[12:13], 1, s[4:5]
	s_waitcnt lgkmcnt(0)
	v_add_f32_e32 v14, v14, v15
	ds_bpermute_b32 v15, v101, v14
	global_store_short v[12:13], v24, off offset:128 sc1
	global_store_short v[12:13], v25, off offset:192 sc1
	s_and_b64 vcc, exec, s[70:71]
	s_waitcnt lgkmcnt(0)
	v_add_f32_e32 v14, v14, v15
	ds_bpermute_b32 v15, v102, v14
	s_waitcnt lgkmcnt(0)
	v_add_f32_e32 v14, v14, v15
	ds_bpermute_b32 v15, v103, v14
	s_waitcnt lgkmcnt(0)
	v_add_f32_e32 v14, v14, v15
	ds_bpermute_b32 v15, v104, v14
	s_waitcnt lgkmcnt(0)
	v_add_f32_e32 v14, v14, v15
	v_fmamk_f32 v14, v14, 0x3c800000, v196
	v_rsq_f32_e32 v14, v14
	s_nop 0
	v_pk_mul_f32 v[12:13], v[10:11], v[14:15] op_sel_hi:[1,0]
	s_nop 0
	v_pk_mul_f32 v[12:13], v[22:23], v[12:13]
	s_cbranch_vccz .LBB0_941
	v_lshl_or_b32 v14, v107, 10, v47
	v_ashrrev_i32_e32 v15, 31, v14
	v_lshl_add_u64 v[14:15], v[14:15], 2, s[26:27]
	global_store_dword v[14:15], v13, off sc1
	global_store_dword v[14:15], v12, off offset:128 sc1

.LBB0_943:
	v_pk_mul_f32 v[14:15], v[20:21], v[20:21]
	v_ashrrev_i32_e32 v69, 31, v68
	v_add_f32_e32 v14, v15, v14
	ds_bpermute_b32 v15, v100, v14
	v_cvt_pk_bf16_f32 v22, v13, s0
	v_cvt_pk_bf16_f32 v23, v12, s0
	v_lshl_add_u64 v[12:13], v[68:69], 0, v[134:135]
	v_lshl_add_u64 v[12:13], v[12:13], 1, s[4:5]
	s_waitcnt lgkmcnt(0)
	v_add_f32_e32 v14, v14, v15
	ds_bpermute_b32 v15, v101, v14
	global_store_short v[12:13], v22, off offset:128 sc1
	global_store_short v[12:13], v23, off offset:192 sc1
	s_and_b64 vcc, exec, s[70:71]
	s_waitcnt lgkmcnt(0)
	v_add_f32_e32 v14, v14, v15
	ds_bpermute_b32 v15, v102, v14
	s_waitcnt lgkmcnt(0)
	v_add_f32_e32 v14, v14, v15
	ds_bpermute_b32 v15, v103, v14
	s_waitcnt lgkmcnt(0)
	v_add_f32_e32 v14, v14, v15
	ds_bpermute_b32 v15, v104, v14
	s_waitcnt lgkmcnt(0)
	v_add_f32_e32 v14, v14, v15
	v_fmamk_f32 v14, v14, 0x3c800000, v196
	v_rsq_f32_e32 v14, v14
	s_nop 0
	v_pk_mul_f32 v[12:13], v[10:11], v[14:15] op_sel_hi:[1,0]
	s_nop 0
	v_pk_mul_f32 v[12:13], v[20:21], v[12:13]
	s_cbranch_vccz .LBB0_945
	v_lshl_or_b32 v14, v108, 10, v47
	v_ashrrev_i32_e32 v15, 31, v14
	v_lshl_add_u64 v[14:15], v[14:15], 2, s[26:27]
	global_store_dword v[14:15], v13, off sc1
	global_store_dword v[14:15], v12, off offset:128 sc1

.LBB0_947:
	v_pk_mul_f32 v[14:15], v[18:19], v[18:19]
	v_ashrrev_i32_e32 v67, 31, v66
	v_add_f32_e32 v14, v15, v14
	ds_bpermute_b32 v15, v100, v14
	v_cvt_pk_bf16_f32 v20, v13, s0
	v_cvt_pk_bf16_f32 v21, v12, s0
	v_lshl_add_u64 v[12:13], v[66:67], 0, v[134:135]
	v_lshl_add_u64 v[12:13], v[12:13], 1, s[4:5]
	s_waitcnt lgkmcnt(0)
	v_add_f32_e32 v14, v14, v15
	ds_bpermute_b32 v15, v101, v14
	global_store_short v[12:13], v20, off offset:128 sc1
	global_store_short v[12:13], v21, off offset:192 sc1
	s_and_b64 vcc, exec, s[70:71]
	s_waitcnt lgkmcnt(0)
	v_add_f32_e32 v14, v14, v15
	ds_bpermute_b32 v15, v102, v14
	s_waitcnt lgkmcnt(0)
	v_add_f32_e32 v14, v14, v15
	ds_bpermute_b32 v15, v103, v14
	s_waitcnt lgkmcnt(0)
	v_add_f32_e32 v14, v14, v15
	ds_bpermute_b32 v15, v104, v14
	s_waitcnt lgkmcnt(0)
	v_add_f32_e32 v14, v14, v15
	v_fmamk_f32 v14, v14, 0x3c800000, v196
	v_rsq_f32_e32 v14, v14
	s_nop 0
	v_pk_mul_f32 v[12:13], v[10:11], v[14:15] op_sel_hi:[1,0]
	s_nop 0
	v_pk_mul_f32 v[12:13], v[18:19], v[12:13]
	s_cbranch_vccz .LBB0_949
	v_lshl_or_b32 v14, v109, 10, v47
	v_ashrrev_i32_e32 v15, 31, v14
	v_lshl_add_u64 v[14:15], v[14:15], 2, s[26:27]
	global_store_dword v[14:15], v13, off sc1
	global_store_dword v[14:15], v12, off offset:128 sc1

.LBB0_951:
	v_pk_mul_f32 v[14:15], v[16:17], v[16:17]
	v_ashrrev_i32_e32 v65, 31, v64
	v_add_f32_e32 v14, v15, v14
	ds_bpermute_b32 v15, v100, v14
	v_cvt_pk_bf16_f32 v18, v13, s0
	v_cvt_pk_bf16_f32 v19, v12, s0
	v_lshl_add_u64 v[12:13], v[64:65], 0, v[134:135]
	v_lshl_add_u64 v[12:13], v[12:13], 1, s[4:5]
	s_waitcnt lgkmcnt(0)
	v_add_f32_e32 v14, v14, v15
	ds_bpermute_b32 v15, v101, v14
	global_store_short v[12:13], v18, off offset:128 sc1
	global_store_short v[12:13], v19, off offset:192 sc1
	s_and_b64 vcc, exec, s[70:71]
	s_waitcnt lgkmcnt(0)
	v_add_f32_e32 v14, v14, v15
	ds_bpermute_b32 v15, v102, v14
	s_waitcnt lgkmcnt(0)
	v_add_f32_e32 v14, v14, v15
	ds_bpermute_b32 v15, v103, v14
	s_waitcnt lgkmcnt(0)
	v_add_f32_e32 v14, v14, v15
	ds_bpermute_b32 v15, v104, v14
	s_waitcnt lgkmcnt(0)
	v_add_f32_e32 v14, v14, v15
	v_fmamk_f32 v14, v14, 0x3c800000, v196
	v_rsq_f32_e32 v14, v14
	s_nop 0
	v_pk_mul_f32 v[12:13], v[10:11], v[14:15] op_sel_hi:[1,0]
	s_nop 0
	v_pk_mul_f32 v[12:13], v[16:17], v[12:13]
	s_cbranch_vccz .LBB0_953
	v_lshl_or_b32 v14, v110, 10, v47
	v_ashrrev_i32_e32 v15, 31, v14
	v_lshl_add_u64 v[14:15], v[14:15], 2, s[26:27]
	global_store_dword v[14:15], v13, off sc1
	global_store_dword v[14:15], v12, off offset:128 sc1

.LBB0_955:
	v_pk_mul_f32 v[14:15], v[8:9], v[8:9]
	v_ashrrev_i32_e32 v57, 31, v56
	v_add_f32_e32 v14, v15, v14
	ds_bpermute_b32 v15, v100, v14
	v_cvt_pk_bf16_f32 v16, v13, s0
	v_cvt_pk_bf16_f32 v17, v12, s0
	v_lshl_add_u64 v[12:13], v[56:57], 0, v[134:135]
	v_lshl_add_u64 v[12:13], v[12:13], 1, s[4:5]
	s_waitcnt lgkmcnt(0)
	v_add_f32_e32 v14, v14, v15
	ds_bpermute_b32 v15, v101, v14
	global_store_short v[12:13], v16, off offset:128 sc1
	global_store_short v[12:13], v17, off offset:192 sc1
	s_and_b64 vcc, exec, s[70:71]
	s_waitcnt lgkmcnt(0)
	v_add_f32_e32 v14, v14, v15
	ds_bpermute_b32 v15, v102, v14
	s_waitcnt lgkmcnt(0)
	v_add_f32_e32 v14, v14, v15
	ds_bpermute_b32 v15, v103, v14
	s_waitcnt lgkmcnt(0)
	v_add_f32_e32 v14, v14, v15
	ds_bpermute_b32 v15, v104, v14
	s_waitcnt lgkmcnt(0)
	v_add_f32_e32 v14, v14, v15
	v_fmamk_f32 v14, v14, 0x3c800000, v196
	v_rsq_f32_e32 v14, v14
	s_nop 0
	v_pk_mul_f32 v[12:13], v[10:11], v[14:15] op_sel_hi:[1,0]
	s_nop 0
	v_pk_mul_f32 v[8:9], v[8:9], v[12:13]
	s_cbranch_vccz .LBB0_957
	v_lshl_or_b32 v12, v111, 10, v47
	v_ashrrev_i32_e32 v13, 31, v12
	v_lshl_add_u64 v[12:13], v[12:13], 2, s[26:27]
	global_store_dword v[12:13], v9, off sc1
	global_store_dword v[12:13], v8, off offset:128 sc1

.LBB0_959:
	v_pk_mul_f32 v[12:13], v[6:7], v[6:7]
	v_ashrrev_i32_e32 v55, 31, v54
	v_add_f32_e32 v12, v13, v12
	ds_bpermute_b32 v13, v100, v12
	v_cvt_pk_bf16_f32 v14, v9, s0
	v_cvt_pk_bf16_f32 v15, v8, s0
	v_lshl_add_u64 v[8:9], v[54:55], 0, v[134:135]
	v_lshl_add_u64 v[8:9], v[8:9], 1, s[4:5]
	s_waitcnt lgkmcnt(0)
	v_add_f32_e32 v12, v12, v13
	ds_bpermute_b32 v13, v101, v12
	global_store_short v[8:9], v14, off offset:128 sc1
	global_store_short v[8:9], v15, off offset:192 sc1
	s_and_b64 vcc, exec, s[70:71]
	s_waitcnt lgkmcnt(0)
	v_add_f32_e32 v12, v12, v13
	ds_bpermute_b32 v13, v102, v12
	s_waitcnt lgkmcnt(0)
	v_add_f32_e32 v12, v12, v13
	ds_bpermute_b32 v13, v103, v12
	s_waitcnt lgkmcnt(0)
	v_add_f32_e32 v12, v12, v13
	ds_bpermute_b32 v13, v104, v12
	s_waitcnt lgkmcnt(0)
	v_add_f32_e32 v12, v12, v13
	v_fmamk_f32 v12, v12, 0x3c800000, v196
	v_rsq_f32_e32 v12, v12
	s_nop 0
	v_pk_mul_f32 v[8:9], v[10:11], v[12:13] op_sel_hi:[1,0]
	s_nop 0
	v_pk_mul_f32 v[6:7], v[6:7], v[8:9]
	s_cbranch_vccz .LBB0_961
	v_lshl_or_b32 v8, v112, 10, v47
	v_ashrrev_i32_e32 v9, 31, v8
	v_lshl_add_u64 v[8:9], v[8:9], 2, s[26:27]
	global_store_dword v[8:9], v7, off sc1
	global_store_dword v[8:9], v6, off offset:128 sc1

.LBB0_963:
	v_pk_mul_f32 v[8:9], v[4:5], v[4:5]
	v_ashrrev_i32_e32 v53, 31, v52
	v_add_f32_e32 v8, v9, v8
	ds_bpermute_b32 v9, v100, v8
	v_cvt_pk_bf16_f32 v12, v7, s0
	v_cvt_pk_bf16_f32 v13, v6, s0
	v_lshl_add_u64 v[6:7], v[52:53], 0, v[134:135]
	v_lshl_add_u64 v[6:7], v[6:7], 1, s[4:5]
	s_waitcnt lgkmcnt(0)
	v_add_f32_e32 v8, v8, v9
	ds_bpermute_b32 v9, v101, v8
	global_store_short v[6:7], v12, off offset:128 sc1
	global_store_short v[6:7], v13, off offset:192 sc1
	s_and_b64 vcc, exec, s[70:71]
	s_waitcnt lgkmcnt(0)
	v_add_f32_e32 v8, v8, v9
	ds_bpermute_b32 v9, v102, v8
	s_waitcnt lgkmcnt(0)
	v_add_f32_e32 v8, v8, v9
	ds_bpermute_b32 v9, v103, v8
	s_waitcnt lgkmcnt(0)
	v_add_f32_e32 v8, v8, v9
	ds_bpermute_b32 v9, v104, v8
	s_waitcnt lgkmcnt(0)
	v_add_f32_e32 v8, v8, v9
	v_fmamk_f32 v8, v8, 0x3c800000, v196
	v_rsq_f32_e32 v8, v8
	s_nop 0
	v_pk_mul_f32 v[6:7], v[10:11], v[8:9] op_sel_hi:[1,0]
	s_nop 0
	v_pk_mul_f32 v[4:5], v[4:5], v[6:7]
	s_cbranch_vccz .LBB0_965
	v_lshl_or_b32 v6, v113, 10, v47
	v_ashrrev_i32_e32 v7, 31, v6
	v_lshl_add_u64 v[6:7], v[6:7], 2, s[26:27]
	global_store_dword v[6:7], v5, off sc1
	global_store_dword v[6:7], v4, off offset:128 sc1

.LBB0_967:
	v_pk_mul_f32 v[6:7], v[2:3], v[2:3]
	v_ashrrev_i32_e32 v51, 31, v50
	v_add_f32_e32 v6, v7, v6
	ds_bpermute_b32 v7, v100, v6
	v_cvt_pk_bf16_f32 v8, v5, s0
	v_cvt_pk_bf16_f32 v9, v4, s0
	v_lshl_add_u64 v[4:5], v[50:51], 0, v[134:135]
	v_lshl_add_u64 v[4:5], v[4:5], 1, s[4:5]
	s_waitcnt lgkmcnt(0)
	v_add_f32_e32 v6, v6, v7
	ds_bpermute_b32 v7, v101, v6
	global_store_short v[4:5], v8, off offset:128 sc1
	global_store_short v[4:5], v9, off offset:192 sc1
	s_and_b64 vcc, exec, s[70:71]
	s_waitcnt lgkmcnt(0)
	v_add_f32_e32 v6, v6, v7
	ds_bpermute_b32 v7, v102, v6
	s_waitcnt lgkmcnt(0)
	v_add_f32_e32 v6, v6, v7
	ds_bpermute_b32 v7, v103, v6
	s_waitcnt lgkmcnt(0)
	v_add_f32_e32 v6, v6, v7
	ds_bpermute_b32 v7, v104, v6
	s_waitcnt lgkmcnt(0)
	v_add_f32_e32 v6, v6, v7
	v_fmamk_f32 v6, v6, 0x3c800000, v196
	v_rsq_f32_e32 v6, v6
	s_nop 0
	v_pk_mul_f32 v[4:5], v[10:11], v[6:7] op_sel_hi:[1,0]
	s_nop 0
	v_pk_mul_f32 v[2:3], v[2:3], v[4:5]
	s_cbranch_vccz .LBB0_969
	v_lshl_or_b32 v4, v114, 10, v47
	v_ashrrev_i32_e32 v5, 31, v4
	v_lshl_add_u64 v[4:5], v[4:5], 2, s[26:27]
	global_store_dword v[4:5], v3, off sc1
	global_store_dword v[4:5], v2, off offset:128 sc1

.LBB0_971:
	v_pk_mul_f32 v[4:5], v[0:1], v[0:1]
	v_ashrrev_i32_e32 v49, 31, v48
	v_add_f32_e32 v4, v5, v4
	ds_bpermute_b32 v5, v100, v4
	v_cvt_pk_bf16_f32 v6, v3, s0
	v_cvt_pk_bf16_f32 v7, v2, s0
	v_lshl_add_u64 v[2:3], v[48:49], 0, v[134:135]
	v_lshl_add_u64 v[2:3], v[2:3], 1, s[4:5]
	s_waitcnt lgkmcnt(0)
	v_add_f32_e32 v4, v4, v5
	ds_bpermute_b32 v5, v101, v4
	global_store_short v[2:3], v6, off offset:128 sc1
	global_store_short v[2:3], v7, off offset:192 sc1
	s_and_b64 vcc, exec, s[70:71]
	s_waitcnt lgkmcnt(0)
	v_add_f32_e32 v4, v4, v5
	ds_bpermute_b32 v5, v102, v4
	s_waitcnt lgkmcnt(0)
	v_add_f32_e32 v4, v4, v5
	ds_bpermute_b32 v5, v103, v4
	s_waitcnt lgkmcnt(0)
	v_add_f32_e32 v4, v4, v5
	ds_bpermute_b32 v5, v104, v4
	s_waitcnt lgkmcnt(0)
	v_add_f32_e32 v4, v4, v5
	v_fmamk_f32 v4, v4, 0x3c800000, v196
	v_rsq_f32_e32 v4, v4
	s_nop 0
	v_pk_mul_f32 v[2:3], v[10:11], v[4:5] op_sel_hi:[1,0]
	s_nop 0
	v_pk_mul_f32 v[0:1], v[0:1], v[2:3]
	s_cbranch_vccz .LBB0_973
	v_lshl_or_b32 v2, v97, 10, v47
	v_ashrrev_i32_e32 v3, 31, v2
	v_lshl_add_u64 v[2:3], v[2:3], 2, s[26:27]
	global_store_dword v[2:3], v1, off sc1
	global_store_dword v[2:3], v0, off offset:128 sc1

.LBB0_978:
	v_ashrrev_i32_e32 v9, 31, v2
	v_mov_b32_e32 v8, v2
	v_ashrrev_i32_e32 v11, 31, v3
	v_mov_b32_e32 v10, v3
	v_lshl_add_u64 v[12:13], v[8:9], 2, s[20:21]
	v_lshl_add_u64 v[14:15], v[10:11], 2, s[20:21]
	global_load_dword v16, v[12:13], off
	global_load_dword v17, v[14:15], off
	v_lshrrev_b32_e32 v8, 22, v9
	v_lshrrev_b32_e32 v9, 14, v9
	v_lshrrev_b32_e32 v10, 22, v11
	v_lshrrev_b32_e32 v11, 14, v11
	v_add_u32_e32 v9, v2, v9
	v_add_u32_e32 v8, v2, v8
	v_add_u32_e32 v11, v3, v11
	v_ashrrev_i32_e32 v9, 18, v9
	v_add_u32_e32 v10, v3, v10
	v_ashrrev_i32_e32 v12, 10, v8
	v_ashrrev_i32_e32 v11, 18, v11
	v_mul_i32_i24_e32 v9, 0x1100, v9
	v_ashrrev_i32_e32 v13, 10, v10
	v_and_b32_e32 v8, 0xfffffc00, v8
	v_mul_i32_i24_e32 v11, 0x1100, v11
	v_or_b32_sdwa v9, v9, v12 dst_sel:DWORD dst_unused:UNUSED_PAD src0_sel:DWORD src1_sel:BYTE_0
	v_and_b32_e32 v10, 0xfffffc00, v10
	v_sub_u32_e32 v8, v2, v8
	v_or_b32_sdwa v11, v11, v13 dst_sel:DWORD dst_unused:UNUSED_PAD src0_sel:DWORD src1_sel:BYTE_0
	v_lshlrev_b32_e32 v9, 10, v9
	v_add_u32_e32 v5, -2, v5
	v_sub_u32_e32 v10, v3, v10
	v_lshlrev_b32_e32 v11, 10, v11
	v_add3_u32 v8, v9, v8, s10
	v_cmp_eq_u32_e64 s[0:1], 0, v5
	v_add3_u32 v10, v11, v10, s10
	v_ashrrev_i32_e32 v9, 31, v8
	s_or_b64 s[26:27], s[0:1], s[26:27]
	v_add_u32_e32 v3, s9, v3
	v_add_u32_e32 v2, s3, v2
	v_ashrrev_i32_e32 v11, 31, v10
	v_lshl_add_u64 v[8:9], v[8:9], 1, s[22:23]
	v_lshl_add_u64 v[10:11], v[10:11], 1, s[22:23]
	s_waitcnt vmcnt(0)
	v_cvt_pk_bf16_f32 v12, v16, v17
	global_store_short v[8:9], v12, off sc1
	global_store_short_d16_hi v[10:11], v12, off sc1
	s_andn2_b64 exec, exec, s[26:27]
	s_cbranch_execnz .LBB0_978
	s_or_b64 exec, exec, s[26:27]
	v_mad_u64_u32 v[2:3], s[0:1], v4, s8, v[0:1]
	v_cmp_ne_u32_e64 s[0:1], v6, v4
	s_orn2_b64 s[0:1], s[0:1], exec

.LBB0_982:
	v_ashrrev_i32_e32 v3, 31, v2
	v_lshl_add_u64 v[4:5], v[2:3], 2, s[20:21]
	global_load_dword v8, v[4:5], off
	v_lshrrev_b32_e32 v4, 22, v3
	v_lshrrev_b32_e32 v3, 14, v3
	v_add_u32_e32 v3, v2, v3
	v_add_u32_e32 v4, v2, v4
	v_ashrrev_i32_e32 v3, 18, v3
	v_ashrrev_i32_e32 v4, 10, v4
	v_mul_i32_i24_e32 v3, 0x1100, v3
	v_and_or_b32 v3, v4, s3, v3
	v_mul_i32_i24_e32 v5, 0x400, v4
	v_lshlrev_b32_e32 v3, 10, v3
	v_sub_u32_e32 v3, v3, v5
	v_add3_u32 v4, v2, v3, s9
	v_add_u32_e32 v2, s8, v2
	v_ashrrev_i32_e32 v5, 31, v4
	v_cmp_lt_i32_e64 s[0:1], s10, v2
	v_lshl_add_u64 v[4:5], v[4:5], 1, s[22:23]
	s_or_b64 s[26:27], s[0:1], s[26:27]
	s_waitcnt vmcnt(0)
	v_cvt_pk_bf16_f32 v3, v8, s0
	global_store_short v[4:5], v3, off sc1
	s_andn2_b64 exec, exec, s[26:27]
	s_cbranch_execnz .LBB0_982

.LBB0_985:
	v_ashrrev_i32_e32 v11, 31, v4
	v_mov_b32_e32 v10, v4
	v_ashrrev_i32_e32 v13, 31, v5
	v_mov_b32_e32 v12, v5
	v_lshl_add_u64 v[14:15], v[10:11], 2, s[18:19]
	v_lshl_add_u64 v[16:17], v[12:13], 2, s[18:19]
	global_load_dword v1, v[14:15], off
	global_load_dword v9, v[16:17], off
	v_ashrrev_i32_e32 v10, 7, v5
	v_ashrrev_i32_e32 v12, 7, v4
	v_lshrrev_b32_e32 v14, 29, v12
	v_lshrrev_b32_e32 v15, 29, v10
	v_lshrrev_b32_e32 v16, 22, v11
	v_lshrrev_b32_e32 v17, 22, v13
	v_lshrrev_b32_e32 v11, 14, v11
	v_lshrrev_b32_e32 v13, 14, v13
	v_add_u32_e32 v14, v12, v14
	v_add_u32_e32 v15, v10, v15
	v_add_u32_e32 v11, v4, v11
	v_add_u32_e32 v13, v5, v13
	v_and_b32_e32 v14, 0x1fffff8, v14
	v_and_b32_e32 v15, 0x1fffff8, v15
	v_ashrrev_i32_e32 v11, 18, v11
	v_ashrrev_i32_e32 v13, 18, v13
	v_sub_u32_e32 v12, v12, v14
	v_sub_u32_e32 v10, v10, v15
	v_lshlrev_b32_e32 v11, 10, v11
	v_lshlrev_b32_e32 v13, 10, v13
	v_lshl_add_u32 v10, v10, 7, v13
	v_lshl_add_u32 v11, v12, 7, v11
	v_add_u32_e32 v16, v4, v16
	v_add_u32_e32 v17, v5, v17
	v_or_b32_e32 v10, v10, v3
	v_or_b32_e32 v11, v11, v2
	v_ashrrev_i32_e32 v16, 10, v16
	v_ashrrev_i32_e32 v17, 10, v17
	v_mul_lo_u32 v10, v10, s10
	v_mul_lo_u32 v11, v11, s10
	v_or_b32_sdwa v12, v10, v17 dst_sel:DWORD dst_unused:UNUSED_PAD src0_sel:DWORD src1_sel:BYTE_0
	v_or_b32_sdwa v10, v11, v16 dst_sel:DWORD dst_unused:UNUSED_PAD src0_sel:DWORD src1_sel:BYTE_0
	v_add_u32_e32 v8, -2, v8
	v_add_u32_e32 v10, 0x800000, v10
	v_cmp_eq_u32_e32 vcc, 0, v8
	v_add_u32_e32 v12, 0x800000, v12
	v_ashrrev_i32_e32 v11, 31, v10
	v_add_u32_e32 v5, s9, v5
	v_add_u32_e32 v4, s3, v4
	s_or_b64 s[22:23], vcc, s[22:23]
	v_ashrrev_i32_e32 v13, 31, v12
	v_lshl_add_u64 v[10:11], v[10:11], 1, s[0:1]
	v_lshl_add_u64 v[12:13], v[12:13], 1, s[0:1]
	s_waitcnt vmcnt(0)
	v_cvt_pk_bf16_f32 v1, v1, v9
	global_store_short v[10:11], v1, off sc1
	global_store_short_d16_hi v[12:13], v1, off sc1
	s_andn2_b64 exec, exec, s[22:23]
	s_cbranch_execnz .LBB0_985
	s_or_b64 exec, exec, s[22:23]
	v_cmp_ne_u32_e32 vcc, v6, v7
	v_mad_u64_u32 v[0:1], s[10:11], v7, s8, v[0:1]
	s_orn2_b64 s[22:23], vcc, exec

.LBB0_989:
	global_load_dword v1, v[4:5], off
	v_ashrrev_i32_e32 v3, 7, v0
	v_ashrrev_i32_e32 v6, 31, v0
	v_lshrrev_b32_e32 v7, 29, v3
	v_lshrrev_b32_e32 v8, 22, v6
	v_lshrrev_b32_e32 v6, 14, v6
	v_add_u32_e32 v7, v3, v7
	v_add_u32_e32 v6, v0, v6
	v_and_b32_e32 v7, 0x1fff8, v7
	v_lshrrev_b32_e32 v6, 8, v6
	v_sub_u32_e32 v3, v3, v7
	v_and_b32_e32 v6, 0xfffc00, v6
	v_lshl_add_u32 v3, v3, 7, v6
	v_add_u32_e32 v8, v0, v8
	v_or_b32_e32 v3, v3, v2
	v_lshrrev_b32_e32 v8, 10, v8
	v_mul_lo_u32 v3, v3, s3
	v_and_or_b32 v3, v8, s9, v3
	v_add_u32_e32 v0, s8, v0
	v_add_u32_e32 v6, 0x800000, v3
	v_cmp_lt_i32_e32 vcc, s10, v0
	v_ashrrev_i32_e32 v7, 31, v6
	v_lshl_add_u64 v[4:5], v[4:5], 0, s[18:19]
	s_or_b64 s[20:21], vcc, s[20:21]
	v_lshl_add_u64 v[6:7], v[6:7], 1, s[0:1]
	s_waitcnt vmcnt(0)
	v_cvt_pk_bf16_f32 v1, v1, s0
	global_store_short v[6:7], v1, off sc1
	s_andn2_b64 exec, exec, s[20:21]
	s_cbranch_execnz .LBB0_989

.LBB0_991:
	s_cmp_gt_i32 s17, 10
	s_cselect_b64 s[0:1], -1, 0
	s_and_b64 s[4:5], s[6:7], s[0:1]
	s_andn2_b64 vcc, exec, s[4:5]
	s_cbranch_vccnz .LBB0_1003
	s_waitcnt vmcnt(0)
	v_or_b32_e32 v0, v201, v200
	s_movk_i32 s3, 0x3ff
	v_and_or_b32 v0, v0, s3, v199
	v_cmp_eq_u32_e32 vcc, 0, v0
	s_waitcnt lgkmcnt(0)
	s_barrier
	s_and_saveexec_b64 s[4:5], vcc
	s_cbranch_execz .LBB0_1002
	s_add_u32 s6, s14, 0x5be8c00
	s_addc_u32 s7, s15, 0
	s_lshl_b32 s3, s2, 1
	v_mov_b32_e32 v0, s3
	v_mov_b32_e32 v1, 0x930a
	global_store_short v0, v1, s[6:7] sc1
	s_cmp_lg_u32 s2, 0
	s_cbranch_scc1 .Lgbar_wait_9
	s_lshr_b32 s3, s33, 3
	s_bfm_b64 s[8:9], s3, 0
	s_cmpk_gt_u32 s33, 0x1ff
	s_cselect_b64 s[8:9], -1, s[8:9]
	s_mov_b64 exec, -1
	v_mbcnt_lo_u32_b32 v229, -1, 0
	v_mbcnt_hi_u32_b32 v229, -1, v229
	v_lshlrev_b32_e32 v229, 4, v229
	s_mov_b32 s10, 0x930a930a
	s_mov_b64 exec, s[8:9]

.LBB0_1026:
	ds_bpermute_b32 v1, v184, v196
	s_mov_b64 s[28:29], -1
	s_waitcnt lgkmcnt(0)
	v_add_f32_e32 v1, v196, v1
	v_div_scale_f32 v2, s[0:1], v1, v1, 1.0
	v_rcp_f32_e32 v3, v2
	v_div_scale_f32 v4, vcc, 1.0, v1, 1.0
	s_and_b64 s[0:1], exec, s[26:27]
	v_fma_f32 v5, -v2, v3, 1.0
	v_fmac_f32_e32 v3, v5, v3
	v_mul_f32_e32 v5, v4, v3
	v_fma_f32 v6, -v2, v5, v4
	v_fmac_f32_e32 v5, v6, v3
	v_fma_f32 v2, -v2, v5, v4
	v_div_fmas_f32 v2, v2, v3, v5
	v_div_fixup_f32 v6, v2, v1, 1.0
	s_mov_b64 vcc, s[0:1]
	s_cbranch_vccz .LBB0_1028
	v_mov_b32_e32 v1, s11
	ds_read_b64 v[2:3], v1
	s_waitcnt lgkmcnt(0)
	v_readfirstlane_b32 s0, v2
	v_readfirstlane_b32 s1, v3
	s_nop 4
	global_load_dword v1, v191, s[0:1]
	global_load_dword v2, v191, s[0:1] offset:256
	global_load_dword v3, v191, s[0:1] offset:512
	global_load_dword v4, v191, s[0:1] offset:768
	s_waitcnt vmcnt(2)
	v_mul_f32_e32 v5, v1, v2
	ds_bpermute_b32 v12, v185, v5
	s_waitcnt vmcnt(0)
	v_mul_f32_e32 v7, v3, v4
	ds_bpermute_b32 v7, v185, v7
	s_waitcnt lgkmcnt(1)
	v_fmac_f32_e32 v12, v1, v2
	ds_bpermute_b32 v1, v186, v12
	s_waitcnt lgkmcnt(1)
	v_fmac_f32_e32 v7, v3, v4
	ds_bpermute_b32 v13, v186, v7
	ds_read2st64_b32 v[2:3], v139 offset0:108 offset1:109
	ds_read2st64_b32 v[4:5], v139 offset0:110 offset1:111
	ds_read2st64_b32 v[8:9], v139 offset0:112 offset1:113
	ds_read2st64_b32 v[10:11], v139 offset0:114 offset1:115
	s_waitcnt lgkmcnt(5)
	v_add_f32_e32 v1, v12, v1
	ds_bpermute_b32 v12, v187, v1
	s_waitcnt lgkmcnt(5)
	v_add_f32_e32 v7, v7, v13
	ds_bpermute_b32 v13, v187, v7
	s_waitcnt lgkmcnt(5)
	v_lshlrev_b32_e32 v96, 16, v2
	v_and_b32_e32 v97, 0xffff0000, v2
	s_waitcnt lgkmcnt(1)
	v_add_f32_e32 v1, v1, v12
	v_lshlrev_b32_e32 v98, 16, v3
	s_waitcnt lgkmcnt(0)
	v_add_f32_e32 v2, v7, v13
	ds_bpermute_b32 v7, v188, v1
	ds_bpermute_b32 v12, v188, v2
	v_and_b32_e32 v99, 0xffff0000, v3
	v_lshlrev_b32_e32 v100, 16, v4
	v_and_b32_e32 v101, 0xffff0000, v4
	s_waitcnt lgkmcnt(1)
	v_add_f32_e32 v1, v1, v7
	s_waitcnt lgkmcnt(0)
	v_add_f32_e32 v2, v2, v12
	ds_bpermute_b32 v3, v189, v1
	ds_bpermute_b32 v4, v189, v2
	v_lshlrev_b32_e32 v7, 16, v5
	v_and_b32_e32 v102, 0xffff0000, v5
	v_lshlrev_b32_e32 v103, 16, v8
	s_waitcnt lgkmcnt(1)
	v_add_f32_e32 v1, v1, v3
	s_waitcnt lgkmcnt(0)
	v_add_f32_e32 v2, v2, v4
	ds_bpermute_b32 v3, v184, v1
	ds_bpermute_b32 v4, v184, v2
	v_and_b32_e32 v104, 0xffff0000, v8
	v_lshlrev_b32_e32 v105, 16, v9
	v_and_b32_e32 v9, 0xffff0000, v9
	s_waitcnt lgkmcnt(1)
	v_add_f32_e32 v1, v1, v3
	s_waitcnt lgkmcnt(0)
	v_add_f32_e32 v2, v2, v4
	v_mul_f32_e32 v1, 0x3fb8aa3b, v1
	v_mul_f32_e32 v2, 0x3fb8aa3b, v2
	v_exp_f32_e32 v1, v1
	v_exp_f32_e32 v2, v2
	v_lshlrev_b32_e32 v106, 16, v10
	v_and_b32_e32 v107, 0xffff0000, v10
	v_lshlrev_b32_e32 v108, 16, v11
	v_sub_f32_e32 v1, v1, v2
	v_add_f32_e32 v1, 0x3eb60549, v1
	v_mul_f32_e32 v8, v6, v1
	v_and_b32_e32 v109, 0xffff0000, v11
	ds_read2st64_b32 v[2:3], v139 offset0:116 offset1:117
	ds_read2st64_b32 v[4:5], v139 offset0:118 offset1:119
	ds_read2st64_b32 v[10:11], v139 offset0:120 offset1:121
	ds_read2st64_b32 v[12:13], v139 offset0:122 offset1:123
	s_waitcnt lgkmcnt(3)
	v_lshlrev_b32_e32 v110, 16, v2
	v_and_b32_e32 v111, 0xffff0000, v2
	v_lshlrev_b32_e32 v112, 16, v3
	v_and_b32_e32 v113, 0xffff0000, v3
	s_waitcnt lgkmcnt(2)
	v_lshlrev_b32_e32 v114, 16, v4
	v_and_b32_e32 v115, 0xffff0000, v4
	v_lshlrev_b32_e32 v116, 16, v5
	v_and_b32_e32 v117, 0xffff0000, v5
	s_waitcnt lgkmcnt(1)
	v_lshlrev_b32_e32 v118, 16, v10
	v_and_b32_e32 v119, 0xffff0000, v10
	v_lshlrev_b32_e32 v120, 16, v11
	v_and_b32_e32 v121, 0xffff0000, v11
	s_waitcnt lgkmcnt(0)
	v_lshlrev_b32_e32 v122, 16, v12
	v_and_b32_e32 v123, 0xffff0000, v12
	v_lshlrev_b32_e32 v124, 16, v13
	v_and_b32_e32 v125, 0xffff0000, v13
	ds_read2st64_b32 v[2:3], v139 offset0:124 offset1:125
	ds_read2st64_b32 v[4:5], v139 offset0:126 offset1:127
	ds_read2st64_b32 v[10:11], v139 offset0:128 offset1:129
	ds_read2st64_b32 v[12:13], v139 offset0:130 offset1:131
	s_waitcnt lgkmcnt(3)
	v_lshlrev_b32_e32 v126, 16, v2
	v_and_b32_e32 v127, 0xffff0000, v2
	v_lshlrev_b32_e32 v128, 16, v3
	v_and_b32_e32 v129, 0xffff0000, v3
	s_waitcnt lgkmcnt(2)
	v_lshlrev_b32_e32 v130, 16, v4
	v_and_b32_e32 v131, 0xffff0000, v4
	v_lshlrev_b32_e32 v132, 16, v5
	v_and_b32_e32 v133, 0xffff0000, v5
	s_waitcnt lgkmcnt(1)
	v_lshlrev_b32_e32 v134, 16, v10
	v_and_b32_e32 v135, 0xffff0000, v10
	v_lshlrev_b32_e32 v170, 16, v11
	v_and_b32_e32 v171, 0xffff0000, v11
	s_waitcnt lgkmcnt(0)
	v_lshlrev_b32_e32 v172, 16, v12
	v_and_b32_e32 v173, 0xffff0000, v12
	v_lshlrev_b32_e32 v174, 16, v13
	v_and_b32_e32 v175, 0xffff0000, v13
	ds_read2st64_b32 v[2:3], v139 offset0:132 offset1:133
	ds_read2st64_b32 v[4:5], v139 offset0:134 offset1:135
	ds_read2st64_b32 v[10:11], v139 offset0:136 offset1:137
	ds_read_b32 v1, v139 offset:35328
	v_mov_b32_e32 v12, v20
	s_waitcnt lgkmcnt(3)
	v_lshlrev_b32_e32 v176, 16, v2
	v_and_b32_e32 v177, 0xffff0000, v2
	v_lshlrev_b32_e32 v178, 16, v3
	v_and_b32_e32 v179, 0xffff0000, v3
	s_waitcnt lgkmcnt(2)
	v_lshlrev_b32_e32 v3, 16, v5
	v_lshlrev_b32_e32 v2, 16, v4
	v_mov_b32_e32 v13, v22
	v_pk_mul_f32 v[82:83], v[12:13], v[8:9] op_sel_hi:[1,0]
	v_pk_fma_f32 v[2:3], v[12:13], v[8:9], v[2:3] op_sel_hi:[1,0,1] neg_lo:[1,0,0] neg_hi:[1,0,0]
	v_and_b32_e32 v5, 0xffff0000, v5
	v_and_b32_e32 v4, 0xffff0000, v4
	v_mov_b32_e32 v12, v21
	v_mov_b32_e32 v13, v23
	v_pk_fma_f32 v[4:5], v[12:13], v[8:9], v[4:5] op_sel_hi:[1,0,1] neg_lo:[1,0,0] neg_hi:[1,0,0]
	v_pk_mul_f32 v[84:85], v[12:13], v[8:9] op_sel_hi:[1,0]
	v_pk_mul_f32 v[4:5], v[4:5], v[4:5]
	ds_read_b32 v12, v195 offset:27648
	v_pk_fma_f32 v[86:87], v[2:3], v[2:3], v[4:5]
	s_waitcnt lgkmcnt(2)
	v_lshlrev_b32_e32 v3, 16, v11
	v_lshlrev_b32_e32 v2, 16, v10
	v_mov_b32_e32 v4, v24
	v_mov_b32_e32 v5, v26
	v_pk_mul_f32 v[14:15], v[4:5], v[8:9] op_sel_hi:[1,0]
	v_pk_fma_f32 v[2:3], v[4:5], v[8:9], v[2:3] op_sel_hi:[1,0,1] neg_lo:[1,0,0] neg_hi:[1,0,0]
	v_and_b32_e32 v5, 0xffff0000, v11
	v_and_b32_e32 v4, 0xffff0000, v10
	v_mov_b32_e32 v10, v25
	v_mov_b32_e32 v11, v27
	v_pk_fma_f32 v[4:5], v[10:11], v[8:9], v[4:5] op_sel_hi:[1,0,1] neg_lo:[1,0,0] neg_hi:[1,0,0]
	v_pk_mul_f32 v[80:81], v[10:11], v[8:9] op_sel_hi:[1,0]
	v_pk_mul_f32 v[4:5], v[4:5], v[4:5]
	v_mov_b32_e32 v90, v29
	v_pk_fma_f32 v[88:89], v[2:3], v[2:3], v[4:5]
	s_waitcnt lgkmcnt(0)
	v_lshlrev_b32_e32 v3, 16, v12
	v_lshlrev_b32_e32 v2, 16, v1
	v_mov_b32_e32 v4, v28
	v_mov_b32_e32 v5, v30
	v_pk_mul_f32 v[10:11], v[4:5], v[8:9] op_sel_hi:[1,0]
	v_pk_fma_f32 v[2:3], v[4:5], v[8:9], v[2:3] op_sel_hi:[1,0,1] neg_lo:[1,0,0] neg_hi:[1,0,0]
	v_and_b32_e32 v5, 0xffff0000, v12
	v_and_b32_e32 v4, 0xffff0000, v1
	v_mov_b32_e32 v91, v31
	v_pk_fma_f32 v[4:5], v[90:91], v[8:9], v[4:5] op_sel_hi:[1,0,1] neg_lo:[1,0,0] neg_hi:[1,0,0]
	v_pk_mul_f32 v[12:13], v[90:91], v[8:9] op_sel_hi:[1,0]
	v_pk_mul_f32 v[4:5], v[4:5], v[4:5]
	s_nop 0
	v_pk_fma_f32 v[92:93], v[2:3], v[2:3], v[4:5]
	v_pk_mul_f32 v[94:95], v[66:67], v[8:9] op_sel_hi:[1,0]
	v_mov_b32_e32 v1, s19
	v_sub_f32_e32 v95, v99, v95
	v_sub_f32_e32 v94, v98, v94
	v_mul_f32_e32 v98, v95, v95
	v_fmac_f32_e32 v98, v94, v94
	v_pk_mul_f32 v[94:95], v[64:65], v[8:9] op_sel_hi:[1,0]
	ds_read_b64 v[2:3], v1
	v_sub_f32_e32 v95, v97, v95
	v_sub_f32_e32 v94, v96, v94
	v_mul_f32_e32 v95, v95, v95
	v_fmac_f32_e32 v95, v94, v94
	v_add_f32_e32 v96, v95, v98
	v_pk_mul_f32 v[94:95], v[70:71], v[8:9] op_sel_hi:[1,0]
	v_lshlrev_b32_e32 v1, 2, v140
	v_sub_f32_e32 v7, v7, v94
	v_sub_f32_e32 v94, v102, v95
	v_mul_f32_e32 v97, v94, v94
	v_pk_mul_f32 v[94:95], v[68:69], v[8:9] op_sel_hi:[1,0]
	v_fmac_f32_e32 v97, v7, v7
	v_sub_f32_e32 v7, v100, v94
	v_sub_f32_e32 v94, v101, v95
	v_mul_f32_e32 v94, v94, v94
	v_fmac_f32_e32 v94, v7, v7
	v_add_f32_e32 v7, v94, v96
	v_pk_mul_f32 v[94:95], v[74:75], v[8:9] op_sel_hi:[1,0]
	v_add_f32_e32 v7, v97, v7
	v_sub_f32_e32 v9, v9, v95
	v_sub_f32_e32 v94, v105, v94
	v_mul_f32_e32 v9, v9, v9
	v_fmac_f32_e32 v9, v94, v94
	v_pk_mul_f32 v[94:95], v[72:73], v[8:9] op_sel_hi:[1,0]
	s_waitcnt lgkmcnt(0)
	v_readfirstlane_b32 s0, v2
	v_sub_f32_e32 v95, v104, v95
	v_sub_f32_e32 v94, v103, v94
	v_mul_f32_e32 v95, v95, v95
	v_fmac_f32_e32 v95, v94, v94
	v_readfirstlane_b32 s1, v3
	v_add_f32_e32 v7, v95, v7
	v_pk_mul_f32 v[94:95], v[78:79], v[8:9] op_sel_hi:[1,0]
	v_add_f32_e32 v7, v9, v7
	v_sub_f32_e32 v9, v108, v94
	v_sub_f32_e32 v94, v109, v95
	global_load_dwordx4 v[2:5], v1, s[0:1]
	v_mul_f32_e32 v96, v94, v94
	v_pk_mul_f32 v[94:95], v[76:77], v[8:9] op_sel_hi:[1,0]
	v_fmac_f32_e32 v96, v9, v9
	v_sub_f32_e32 v9, v106, v94
	v_sub_f32_e32 v94, v107, v95
	v_mul_f32_e32 v94, v94, v94
	v_fmac_f32_e32 v94, v9, v9
	v_add_f32_e32 v7, v94, v7
	v_pk_mul_f32 v[94:95], v[50:51], v[8:9] op_sel_hi:[1,0]
	v_add_f32_e32 v7, v96, v7
	v_sub_f32_e32 v9, v112, v94
	v_sub_f32_e32 v94, v113, v95
	v_mul_f32_e32 v96, v94, v94
	v_pk_mul_f32 v[94:95], v[48:49], v[8:9] op_sel_hi:[1,0]
	v_fmac_f32_e32 v96, v9, v9
	v_sub_f32_e32 v9, v110, v94
	v_sub_f32_e32 v94, v111, v95
	v_mul_f32_e32 v94, v94, v94
	v_fmac_f32_e32 v94, v9, v9
	v_add_f32_e32 v7, v94, v7
	v_pk_mul_f32 v[94:95], v[54:55], v[8:9] op_sel_hi:[1,0]
	v_add_f32_e32 v7, v96, v7
	v_sub_f32_e32 v9, v116, v94
	v_sub_f32_e32 v94, v117, v95
	v_mul_f32_e32 v96, v94, v94
	v_pk_mul_f32 v[94:95], v[52:53], v[8:9] op_sel_hi:[1,0]
	v_fmac_f32_e32 v96, v9, v9
	v_sub_f32_e32 v9, v114, v94
	v_sub_f32_e32 v94, v115, v95
	v_mul_f32_e32 v94, v94, v94
	v_fmac_f32_e32 v94, v9, v9
	v_add_f32_e32 v7, v94, v7
	v_pk_mul_f32 v[94:95], v[58:59], v[8:9] op_sel_hi:[1,0]
	v_add_f32_e32 v7, v96, v7
	v_sub_f32_e32 v9, v120, v94
	v_sub_f32_e32 v94, v121, v95
	v_mul_f32_e32 v96, v94, v94
	v_pk_mul_f32 v[94:95], v[56:57], v[8:9] op_sel_hi:[1,0]
	v_fmac_f32_e32 v96, v9, v9
	v_sub_f32_e32 v9, v118, v94
	v_sub_f32_e32 v94, v119, v95
	v_mul_f32_e32 v94, v94, v94
	v_fmac_f32_e32 v94, v9, v9
	v_add_f32_e32 v7, v94, v7
	v_pk_mul_f32 v[94:95], v[62:63], v[8:9] op_sel_hi:[1,0]
	v_add_f32_e32 v7, v96, v7
	v_sub_f32_e32 v9, v124, v94
	v_sub_f32_e32 v94, v125, v95
	v_mul_f32_e32 v96, v94, v94
	v_pk_mul_f32 v[94:95], v[60:61], v[8:9] op_sel_hi:[1,0]
	v_fmac_f32_e32 v96, v9, v9
	v_sub_f32_e32 v9, v122, v94
	v_sub_f32_e32 v94, v123, v95
	v_mul_f32_e32 v94, v94, v94
	v_fmac_f32_e32 v94, v9, v9
	v_add_f32_e32 v7, v94, v7
	v_pk_mul_f32 v[94:95], v[34:35], v[8:9] op_sel_hi:[1,0]
	v_add_f32_e32 v7, v96, v7
	v_sub_f32_e32 v9, v128, v94
	v_sub_f32_e32 v94, v129, v95
	v_mul_f32_e32 v96, v94, v94
	v_pk_mul_f32 v[94:95], v[32:33], v[8:9] op_sel_hi:[1,0]
	v_fmac_f32_e32 v96, v9, v9
	v_sub_f32_e32 v9, v126, v94
	v_sub_f32_e32 v94, v127, v95
	v_mul_f32_e32 v94, v94, v94
	v_fmac_f32_e32 v94, v9, v9
	v_add_f32_e32 v7, v94, v7
	v_pk_mul_f32 v[94:95], v[38:39], v[8:9] op_sel_hi:[1,0]
	v_add_f32_e32 v7, v96, v7
	v_sub_f32_e32 v9, v132, v94
	v_sub_f32_e32 v94, v133, v95
	v_mul_f32_e32 v96, v94, v94
	v_pk_mul_f32 v[94:95], v[36:37], v[8:9] op_sel_hi:[1,0]
	v_fmac_f32_e32 v96, v9, v9
	v_sub_f32_e32 v9, v130, v94
	v_sub_f32_e32 v94, v131, v95
	v_mul_f32_e32 v94, v94, v94
	v_fmac_f32_e32 v94, v9, v9
	v_add_f32_e32 v7, v94, v7
	v_pk_mul_f32 v[94:95], v[42:43], v[8:9] op_sel_hi:[1,0]
	v_add_f32_e32 v7, v96, v7
	v_sub_f32_e32 v9, v170, v94
	v_sub_f32_e32 v94, v171, v95
	v_mul_f32_e32 v96, v94, v94
	v_pk_mul_f32 v[94:95], v[40:41], v[8:9] op_sel_hi:[1,0]
	v_fmac_f32_e32 v96, v9, v9
	v_sub_f32_e32 v9, v134, v94
	v_sub_f32_e32 v94, v135, v95
	v_mul_f32_e32 v94, v94, v94
	v_fmac_f32_e32 v94, v9, v9
	v_add_f32_e32 v7, v94, v7
	v_pk_mul_f32 v[94:95], v[46:47], v[8:9] op_sel_hi:[1,0]
	v_add_f32_e32 v7, v96, v7
	v_sub_f32_e32 v9, v174, v94
	v_sub_f32_e32 v94, v175, v95
	v_mul_f32_e32 v96, v94, v94
	v_pk_mul_f32 v[94:95], v[44:45], v[8:9] op_sel_hi:[1,0]
	v_fmac_f32_e32 v96, v9, v9
	v_sub_f32_e32 v9, v172, v94
	v_sub_f32_e32 v94, v173, v95
	v_mul_f32_e32 v94, v94, v94
	v_fmac_f32_e32 v94, v9, v9
	v_add_f32_e32 v7, v94, v7
	v_pk_mul_f32 v[94:95], v[18:19], v[8:9] op_sel_hi:[1,0]
	v_add_f32_e32 v7, v96, v7
	v_sub_f32_e32 v9, v178, v94
	v_sub_f32_e32 v94, v179, v95
	v_mul_f32_e32 v96, v94, v94
	v_pk_mul_f32 v[94:95], v[16:17], v[8:9] op_sel_hi:[1,0]
	v_fmac_f32_e32 v96, v9, v9
	v_sub_f32_e32 v9, v176, v94
	v_sub_f32_e32 v94, v177, v95
	v_mul_f32_e32 v94, v94, v94
	v_fmac_f32_e32 v94, v9, v9
	v_add_f32_e32 v7, v7, v94
	v_add_f32_e32 v7, v7, v96
	v_add_f32_e32 v7, v7, v86
	v_add_f32_e32 v7, v7, v87
	v_add_f32_e32 v7, v7, v88
	v_add_f32_e32 v7, v7, v89
	v_add_f32_e32 v7, v7, v92
	v_add_f32_e32 v7, v7, v93
	ds_bpermute_b32 v9, v184, v7
	ds_read2st64_b32 v[90:91], v139 offset0:108 offset1:109
	ds_read2st64_b32 v[88:89], v139 offset0:110 offset1:111
	ds_read2st64_b32 v[92:93], v139 offset0:112 offset1:113
	ds_read2st64_b32 v[94:95], v139 offset0:114 offset1:115
	s_waitcnt lgkmcnt(4)
	v_add_f32_e32 v7, v7, v9
	v_fmamk_f32 v7, v7, 0x3c000000, v192
	v_rsq_f32_e32 v7, v7
	s_waitcnt lgkmcnt(3)
	v_lshlrev_b32_e32 v86, 16, v90
	v_and_b32_e32 v87, 0xffff0000, v90
	v_lshlrev_b32_e32 v90, 16, v91
	v_and_b32_e32 v91, 0xffff0000, v91
	v_pk_fma_f32 v[96:97], v[64:65], v[8:9], v[86:87] op_sel_hi:[1,0,1] neg_lo:[1,0,0] neg_hi:[1,0,0]
	v_pk_fma_f32 v[90:91], v[66:67], v[8:9], v[90:91] op_sel_hi:[1,0,1] neg_lo:[1,0,0] neg_hi:[1,0,0]
	v_mul_f32_e32 v86, 0x3f24fd5c, v7
	v_pk_mul_f32 v[96:97], v[96:97], v[86:87] op_sel_hi:[1,0]
	v_pk_mul_f32 v[90:91], v[86:87], v[90:91] op_sel_hi:[0,1]
	s_waitcnt vmcnt(0)
	v_pk_mul_f32 v[2:3], v[2:3], v[96:97]
	v_pk_mul_f32 v[4:5], v[4:5], v[90:91]
	v_cvt_pk_bf16_f32 v2, v2, v3
	v_cvt_pk_bf16_f32 v3, v4, v5
	global_store_dwordx2 v[150:151], v[2:3], off sc1
	global_load_dwordx4 v[2:5], v1, s[0:1] offset:32
	s_waitcnt lgkmcnt(2)
	v_lshlrev_b32_e32 v90, 16, v88
	v_and_b32_e32 v91, 0xffff0000, v88
	v_lshlrev_b32_e32 v88, 16, v89
	v_and_b32_e32 v89, 0xffff0000, v89
	v_pk_fma_f32 v[90:91], v[68:69], v[8:9], v[90:91] op_sel_hi:[1,0,1] neg_lo:[1,0,0] neg_hi:[1,0,0]
	v_pk_fma_f32 v[88:89], v[70:71], v[8:9], v[88:89] op_sel_hi:[1,0,1] neg_lo:[1,0,0] neg_hi:[1,0,0]
	v_pk_mul_f32 v[90:91], v[86:87], v[90:91] op_sel_hi:[0,1]
	v_pk_mul_f32 v[88:89], v[86:87], v[88:89] op_sel_hi:[0,1]
	s_waitcnt vmcnt(0)
	v_pk_mul_f32 v[2:3], v[2:3], v[90:91]
	v_pk_mul_f32 v[4:5], v[4:5], v[88:89]
	v_cvt_pk_bf16_f32 v2, v2, v3
	v_cvt_pk_bf16_f32 v3, v4, v5
	global_store_dwordx2 v[150:151], v[2:3], off offset:16 sc1
	global_load_dwordx4 v[2:5], v1, s[0:1] offset:64
	s_waitcnt lgkmcnt(1)
	v_lshlrev_b32_e32 v88, 16, v92
	v_and_b32_e32 v89, 0xffff0000, v92
	v_lshlrev_b32_e32 v90, 16, v93
	v_and_b32_e32 v91, 0xffff0000, v93
	v_pk_fma_f32 v[88:89], v[72:73], v[8:9], v[88:89] op_sel_hi:[1,0,1] neg_lo:[1,0,0] neg_hi:[1,0,0]
	v_pk_fma_f32 v[90:91], v[74:75], v[8:9], v[90:91] op_sel_hi:[1,0,1] neg_lo:[1,0,0] neg_hi:[1,0,0]
	v_pk_mul_f32 v[88:89], v[86:87], v[88:89] op_sel_hi:[0,1]
	v_pk_mul_f32 v[90:91], v[86:87], v[90:91] op_sel_hi:[0,1]
	s_waitcnt vmcnt(0)
	v_pk_mul_f32 v[2:3], v[2:3], v[88:89]
	v_pk_mul_f32 v[4:5], v[4:5], v[90:91]
	v_cvt_pk_bf16_f32 v2, v2, v3
	v_cvt_pk_bf16_f32 v3, v4, v5
	global_store_dwordx2 v[150:151], v[2:3], off offset:32 sc1
	global_load_dwordx4 v[2:5], v1, s[0:1] offset:96
	s_waitcnt lgkmcnt(0)
	v_lshlrev_b32_e32 v88, 16, v94
	v_and_b32_e32 v89, 0xffff0000, v94
	v_lshlrev_b32_e32 v90, 16, v95
	v_and_b32_e32 v91, 0xffff0000, v95
	v_pk_fma_f32 v[88:89], v[76:77], v[8:9], v[88:89] op_sel_hi:[1,0,1] neg_lo:[1,0,0] neg_hi:[1,0,0]
	v_pk_fma_f32 v[90:91], v[78:79], v[8:9], v[90:91] op_sel_hi:[1,0,1] neg_lo:[1,0,0] neg_hi:[1,0,0]
	v_pk_mul_f32 v[88:89], v[86:87], v[88:89] op_sel_hi:[0,1]
	v_pk_mul_f32 v[90:91], v[86:87], v[90:91] op_sel_hi:[0,1]
	s_waitcnt vmcnt(0)
	v_pk_mul_f32 v[2:3], v[2:3], v[88:89]
	v_pk_mul_f32 v[4:5], v[4:5], v[90:91]
	v_cvt_pk_bf16_f32 v2, v2, v3
	v_cvt_pk_bf16_f32 v3, v4, v5
	global_store_dwordx2 v[150:151], v[2:3], off offset:48 sc1
	global_load_dwordx4 v[2:5], v1, s[0:1] offset:128
	ds_read2st64_b32 v[88:89], v139 offset0:116 offset1:117
	ds_read2st64_b32 v[90:91], v139 offset0:118 offset1:119
	ds_read2st64_b32 v[92:93], v139 offset0:120 offset1:121
	ds_read2st64_b32 v[94:95], v139 offset0:122 offset1:123
	s_waitcnt lgkmcnt(3)
	v_lshlrev_b32_e32 v96, 16, v88
	v_and_b32_e32 v97, 0xffff0000, v88
	v_lshlrev_b32_e32 v88, 16, v89
	v_and_b32_e32 v89, 0xffff0000, v89
	v_pk_fma_f32 v[96:97], v[48:49], v[8:9], v[96:97] op_sel_hi:[1,0,1] neg_lo:[1,0,0] neg_hi:[1,0,0]
	v_pk_fma_f32 v[88:89], v[50:51], v[8:9], v[88:89] op_sel_hi:[1,0,1] neg_lo:[1,0,0] neg_hi:[1,0,0]
	v_pk_mul_f32 v[96:97], v[86:87], v[96:97] op_sel_hi:[0,1]
	v_pk_mul_f32 v[88:89], v[86:87], v[88:89] op_sel_hi:[0,1]
	s_waitcnt vmcnt(0)
	v_pk_mul_f32 v[2:3], v[2:3], v[96:97]
	v_pk_mul_f32 v[4:5], v[4:5], v[88:89]
	v_cvt_pk_bf16_f32 v2, v2, v3
	v_cvt_pk_bf16_f32 v3, v4, v5
	global_store_dwordx2 v[150:151], v[2:3], off offset:64 sc1
	global_load_dwordx4 v[2:5], v1, s[0:1] offset:160
	s_waitcnt lgkmcnt(2)
	v_lshlrev_b32_e32 v88, 16, v90
	v_and_b32_e32 v89, 0xffff0000, v90
	v_lshlrev_b32_e32 v90, 16, v91
	v_and_b32_e32 v91, 0xffff0000, v91
	v_pk_fma_f32 v[88:89], v[52:53], v[8:9], v[88:89] op_sel_hi:[1,0,1] neg_lo:[1,0,0] neg_hi:[1,0,0]
	v_pk_fma_f32 v[90:91], v[54:55], v[8:9], v[90:91] op_sel_hi:[1,0,1] neg_lo:[1,0,0] neg_hi:[1,0,0]
	v_pk_mul_f32 v[88:89], v[86:87], v[88:89] op_sel_hi:[0,1]
	v_pk_mul_f32 v[90:91], v[86:87], v[90:91] op_sel_hi:[0,1]
	s_waitcnt vmcnt(0)
	v_pk_mul_f32 v[2:3], v[2:3], v[88:89]
	v_pk_mul_f32 v[4:5], v[4:5], v[90:91]
	v_cvt_pk_bf16_f32 v2, v2, v3
	v_cvt_pk_bf16_f32 v3, v4, v5
	global_store_dwordx2 v[150:151], v[2:3], off offset:80 sc1
	global_load_dwordx4 v[2:5], v1, s[0:1] offset:192
	s_waitcnt lgkmcnt(1)
	v_lshlrev_b32_e32 v88, 16, v92
	v_and_b32_e32 v89, 0xffff0000, v92
	v_lshlrev_b32_e32 v90, 16, v93
	v_and_b32_e32 v91, 0xffff0000, v93
	v_pk_fma_f32 v[88:89], v[56:57], v[8:9], v[88:89] op_sel_hi:[1,0,1] neg_lo:[1,0,0] neg_hi:[1,0,0]
	v_pk_fma_f32 v[90:91], v[58:59], v[8:9], v[90:91] op_sel_hi:[1,0,1] neg_lo:[1,0,0] neg_hi:[1,0,0]
	v_pk_mul_f32 v[88:89], v[86:87], v[88:89] op_sel_hi:[0,1]
	v_pk_mul_f32 v[90:91], v[86:87], v[90:91] op_sel_hi:[0,1]
	s_waitcnt vmcnt(0)
	v_pk_mul_f32 v[2:3], v[2:3], v[88:89]
	v_pk_mul_f32 v[4:5], v[4:5], v[90:91]
	v_cvt_pk_bf16_f32 v2, v2, v3
	v_cvt_pk_bf16_f32 v3, v4, v5
	global_store_dwordx2 v[150:151], v[2:3], off offset:96 sc1
	global_load_dwordx4 v[2:5], v1, s[0:1] offset:224
	s_waitcnt lgkmcnt(0)
	v_lshlrev_b32_e32 v88, 16, v94
	v_and_b32_e32 v89, 0xffff0000, v94
	v_lshlrev_b32_e32 v90, 16, v95
	v_and_b32_e32 v91, 0xffff0000, v95
	v_pk_fma_f32 v[88:89], v[60:61], v[8:9], v[88:89] op_sel_hi:[1,0,1] neg_lo:[1,0,0] neg_hi:[1,0,0]
	v_pk_fma_f32 v[90:91], v[62:63], v[8:9], v[90:91] op_sel_hi:[1,0,1] neg_lo:[1,0,0] neg_hi:[1,0,0]
	v_pk_mul_f32 v[88:89], v[86:87], v[88:89] op_sel_hi:[0,1]
	v_pk_mul_f32 v[90:91], v[86:87], v[90:91] op_sel_hi:[0,1]
	s_waitcnt vmcnt(0)
	v_pk_mul_f32 v[2:3], v[2:3], v[88:89]
	v_pk_mul_f32 v[4:5], v[4:5], v[90:91]
	v_cvt_pk_bf16_f32 v2, v2, v3
	v_cvt_pk_bf16_f32 v3, v4, v5
	global_store_dwordx2 v[150:151], v[2:3], off offset:112 sc1
	global_load_dwordx4 v[2:5], v1, s[0:1] offset:256
	ds_read2st64_b32 v[88:89], v139 offset0:124 offset1:125
	ds_read2st64_b32 v[90:91], v139 offset0:126 offset1:127
	ds_read2st64_b32 v[92:93], v139 offset0:128 offset1:129
	ds_read2st64_b32 v[94:95], v139 offset0:130 offset1:131
	s_waitcnt lgkmcnt(3)
	v_lshlrev_b32_e32 v96, 16, v88
	v_and_b32_e32 v97, 0xffff0000, v88
	v_lshlrev_b32_e32 v88, 16, v89
	v_and_b32_e32 v89, 0xffff0000, v89
	v_pk_fma_f32 v[96:97], v[32:33], v[8:9], v[96:97] op_sel_hi:[1,0,1] neg_lo:[1,0,0] neg_hi:[1,0,0]
	v_pk_fma_f32 v[88:89], v[34:35], v[8:9], v[88:89] op_sel_hi:[1,0,1] neg_lo:[1,0,0] neg_hi:[1,0,0]
	v_pk_mul_f32 v[96:97], v[86:87], v[96:97] op_sel_hi:[0,1]
	v_pk_mul_f32 v[88:89], v[86:87], v[88:89] op_sel_hi:[0,1]
	s_waitcnt vmcnt(0)
	v_pk_mul_f32 v[2:3], v[2:3], v[96:97]
	v_pk_mul_f32 v[4:5], v[4:5], v[88:89]
	v_cvt_pk_bf16_f32 v2, v2, v3
	v_cvt_pk_bf16_f32 v3, v4, v5
	global_store_dwordx2 v[150:151], v[2:3], off offset:128 sc1
	global_load_dwordx4 v[2:5], v1, s[0:1] offset:288
	s_waitcnt lgkmcnt(2)
	v_lshlrev_b32_e32 v88, 16, v90
	v_and_b32_e32 v89, 0xffff0000, v90
	v_lshlrev_b32_e32 v90, 16, v91
	v_and_b32_e32 v91, 0xffff0000, v91
	v_pk_fma_f32 v[88:89], v[36:37], v[8:9], v[88:89] op_sel_hi:[1,0,1] neg_lo:[1,0,0] neg_hi:[1,0,0]
	v_pk_fma_f32 v[90:91], v[38:39], v[8:9], v[90:91] op_sel_hi:[1,0,1] neg_lo:[1,0,0] neg_hi:[1,0,0]
	v_pk_mul_f32 v[88:89], v[86:87], v[88:89] op_sel_hi:[0,1]
	v_pk_mul_f32 v[90:91], v[86:87], v[90:91] op_sel_hi:[0,1]
	s_waitcnt vmcnt(0)
	v_pk_mul_f32 v[2:3], v[2:3], v[88:89]
	v_pk_mul_f32 v[4:5], v[4:5], v[90:91]
	v_cvt_pk_bf16_f32 v2, v2, v3
	v_cvt_pk_bf16_f32 v3, v4, v5
	global_store_dwordx2 v[150:151], v[2:3], off offset:144 sc1
	global_load_dwordx4 v[2:5], v1, s[0:1] offset:320
	s_waitcnt lgkmcnt(1)
	v_lshlrev_b32_e32 v88, 16, v92
	v_and_b32_e32 v89, 0xffff0000, v92
	v_lshlrev_b32_e32 v90, 16, v93
	v_and_b32_e32 v91, 0xffff0000, v93
	v_pk_fma_f32 v[88:89], v[40:41], v[8:9], v[88:89] op_sel_hi:[1,0,1] neg_lo:[1,0,0] neg_hi:[1,0,0]
	v_pk_fma_f32 v[90:91], v[42:43], v[8:9], v[90:91] op_sel_hi:[1,0,1] neg_lo:[1,0,0] neg_hi:[1,0,0]
	v_pk_mul_f32 v[88:89], v[86:87], v[88:89] op_sel_hi:[0,1]
	v_pk_mul_f32 v[90:91], v[86:87], v[90:91] op_sel_hi:[0,1]
	s_waitcnt vmcnt(0)
	v_pk_mul_f32 v[2:3], v[2:3], v[88:89]
	v_pk_mul_f32 v[4:5], v[4:5], v[90:91]
	v_cvt_pk_bf16_f32 v2, v2, v3
	v_cvt_pk_bf16_f32 v3, v4, v5
	global_store_dwordx2 v[150:151], v[2:3], off offset:160 sc1
	global_load_dwordx4 v[2:5], v1, s[0:1] offset:352
	s_waitcnt lgkmcnt(0)
	v_lshlrev_b32_e32 v88, 16, v94
	v_and_b32_e32 v89, 0xffff0000, v94
	v_lshlrev_b32_e32 v90, 16, v95
	v_and_b32_e32 v91, 0xffff0000, v95
	v_pk_fma_f32 v[88:89], v[44:45], v[8:9], v[88:89] op_sel_hi:[1,0,1] neg_lo:[1,0,0] neg_hi:[1,0,0]
	v_pk_fma_f32 v[90:91], v[46:47], v[8:9], v[90:91] op_sel_hi:[1,0,1] neg_lo:[1,0,0] neg_hi:[1,0,0]
	v_pk_mul_f32 v[88:89], v[86:87], v[88:89] op_sel_hi:[0,1]
	v_pk_mul_f32 v[90:91], v[86:87], v[90:91] op_sel_hi:[0,1]
	s_waitcnt vmcnt(0)
	v_pk_mul_f32 v[2:3], v[2:3], v[88:89]
	v_pk_mul_f32 v[4:5], v[4:5], v[90:91]
	v_cvt_pk_bf16_f32 v2, v2, v3
	v_cvt_pk_bf16_f32 v3, v4, v5
	global_store_dwordx2 v[150:151], v[2:3], off offset:176 sc1
	global_load_dwordx4 v[2:5], v1, s[0:1] offset:384
	ds_read2st64_b32 v[88:89], v139 offset0:132 offset1:133
	ds_read2st64_b32 v[90:91], v139 offset0:134 offset1:135
	ds_read2st64_b32 v[92:93], v139 offset0:136 offset1:137
	ds_read2st64_b32 v[94:95], v139 offset0:138 offset1:139
	s_waitcnt lgkmcnt(3)
	v_lshlrev_b32_e32 v96, 16, v88
	v_and_b32_e32 v97, 0xffff0000, v88
	v_lshlrev_b32_e32 v88, 16, v89
	v_and_b32_e32 v89, 0xffff0000, v89
	v_pk_fma_f32 v[96:97], v[16:17], v[8:9], v[96:97] op_sel_hi:[1,0,1] neg_lo:[1,0,0] neg_hi:[1,0,0]
	v_pk_fma_f32 v[8:9], v[18:19], v[8:9], v[88:89] op_sel_hi:[1,0,1] neg_lo:[1,0,0] neg_hi:[1,0,0]
	v_pk_mul_f32 v[88:89], v[86:87], v[96:97] op_sel_hi:[0,1]
	v_pk_mul_f32 v[8:9], v[86:87], v[8:9] op_sel_hi:[0,1]
	s_waitcnt vmcnt(0)
	v_pk_mul_f32 v[2:3], v[2:3], v[88:89]
	v_pk_mul_f32 v[4:5], v[4:5], v[8:9]
	v_cvt_pk_bf16_f32 v2, v2, v3
	v_cvt_pk_bf16_f32 v3, v4, v5
	global_store_dwordx2 v[150:151], v[2:3], off offset:192 sc1
	global_load_dwordx4 v[2:5], v1, s[0:1] offset:416
	v_mov_b32_e32 v8, v82
	v_mov_b32_e32 v9, v84
	v_mov_b32_e32 v84, v83
	s_waitcnt lgkmcnt(2)
	v_lshlrev_b32_e32 v82, 16, v90
	v_and_b32_e32 v83, 0xffff0000, v90
	v_lshlrev_b32_e32 v88, 16, v91
	v_and_b32_e32 v89, 0xffff0000, v91
	v_pk_add_f32 v[8:9], v[82:83], v[8:9] neg_lo:[0,1] neg_hi:[0,1]
	v_pk_add_f32 v[82:83], v[88:89], v[84:85] neg_lo:[0,1] neg_hi:[0,1]
	v_pk_mul_f32 v[8:9], v[86:87], v[8:9] op_sel_hi:[0,1]
	v_pk_mul_f32 v[82:83], v[86:87], v[82:83] op_sel_hi:[0,1]
	s_waitcnt vmcnt(0)
	v_pk_mul_f32 v[2:3], v[2:3], v[8:9]
	v_pk_mul_f32 v[4:5], v[4:5], v[82:83]
	v_cvt_pk_bf16_f32 v2, v2, v3
	v_cvt_pk_bf16_f32 v3, v4, v5
	global_store_dwordx2 v[150:151], v[2:3], off offset:208 sc1
	global_load_dwordx4 v[2:5], v1, s[0:1] offset:448
	v_mov_b32_e32 v8, v14
	v_mov_b32_e32 v9, v80
	v_mov_b32_e32 v80, v15
	s_waitcnt lgkmcnt(1)
	v_lshlrev_b32_e32 v14, 16, v92
	v_and_b32_e32 v15, 0xffff0000, v92
	v_lshlrev_b32_e32 v82, 16, v93
	v_and_b32_e32 v83, 0xffff0000, v93
	v_pk_add_f32 v[8:9], v[14:15], v[8:9] neg_lo:[0,1] neg_hi:[0,1]
	v_pk_add_f32 v[14:15], v[82:83], v[80:81] neg_lo:[0,1] neg_hi:[0,1]
	v_pk_mul_f32 v[8:9], v[86:87], v[8:9] op_sel_hi:[0,1]
	v_pk_mul_f32 v[14:15], v[86:87], v[14:15] op_sel_hi:[0,1]
	s_waitcnt vmcnt(0)
	v_pk_mul_f32 v[2:3], v[2:3], v[8:9]
	v_pk_mul_f32 v[4:5], v[4:5], v[14:15]
	v_cvt_pk_bf16_f32 v2, v2, v3
	v_cvt_pk_bf16_f32 v3, v4, v5
	global_store_dwordx2 v[150:151], v[2:3], off offset:224 sc1
	global_load_dwordx4 v[2:5], v1, s[0:1] offset:480
	v_mov_b32_e32 v8, v10
	v_mov_b32_e32 v9, v12
	v_mov_b32_e32 v12, v11
	s_waitcnt lgkmcnt(0)
	v_lshlrev_b32_e32 v10, 16, v94
	v_and_b32_e32 v11, 0xffff0000, v94
	v_lshlrev_b32_e32 v14, 16, v95
	v_and_b32_e32 v15, 0xffff0000, v95
	v_pk_add_f32 v[8:9], v[10:11], v[8:9] neg_lo:[0,1] neg_hi:[0,1]
	v_pk_add_f32 v[10:11], v[14:15], v[12:13] neg_lo:[0,1] neg_hi:[0,1]
	v_pk_mul_f32 v[8:9], v[86:87], v[8:9] op_sel_hi:[0,1]
	v_pk_mul_f32 v[10:11], v[86:87], v[10:11] op_sel_hi:[0,1]
	s_waitcnt vmcnt(0)
	v_pk_mul_f32 v[2:3], v[2:3], v[8:9]
	v_pk_mul_f32 v[4:5], v[4:5], v[10:11]
	v_cvt_pk_bf16_f32 v2, v2, v3
	v_cvt_pk_bf16_f32 v3, v4, v5
	global_store_dwordx2 v[150:151], v[2:3], off offset:240 sc1
	s_cbranch_execnz .LBB0_1016
	s_branch .LBB0_1029

.LBB0_1030:
	s_cmp_gt_i32 s17, 11
	s_cselect_b64 s[0:1], -1, 0
	s_and_b64 s[4:5], s[4:5], s[0:1]
	s_andn2_b64 vcc, exec, s[4:5]
	s_cbranch_vccnz .LBB0_1042
	s_waitcnt vmcnt(0)
	v_or_b32_e32 v0, v201, v200
	s_movk_i32 s3, 0x3ff
	v_and_or_b32 v0, v0, s3, v199
	v_cmp_eq_u32_e32 vcc, 0, v0
	s_waitcnt lgkmcnt(0)
	s_barrier
	s_and_saveexec_b64 s[4:5], vcc
	s_cbranch_execz .LBB0_1041
	s_add_u32 s6, s14, 0x5be8c00
	s_addc_u32 s7, s15, 0
	s_lshl_b32 s3, s2, 1
	v_mov_b32_e32 v0, s3
	v_mov_b32_e32 v1, 0x930b
	global_store_short v0, v1, s[6:7] sc1
	s_cmp_lg_u32 s2, 0
	s_cbranch_scc1 .Lgbar_wait_10
	s_lshr_b32 s3, s33, 3
	s_bfm_b64 s[8:9], s3, 0
	s_cmpk_gt_u32 s33, 0x1ff
	s_cselect_b64 s[8:9], -1, s[8:9]
	s_mov_b64 exec, -1
	v_mbcnt_lo_u32_b32 v229, -1, 0
	v_mbcnt_hi_u32_b32 v229, -1, v229
	v_lshlrev_b32_e32 v229, 4, v229
	s_mov_b32 s10, 0x930b930b
	s_mov_b64 exec, s[8:9]

.LBB0_1042:
	s_cmp_lt_i32 s16, 12
	s_cselect_b64 s[4:5], -1, 0
	s_and_b64 s[0:1], s[4:5], s[0:1]
	s_andn2_b64 vcc, exec, s[0:1]
	s_cbranch_vccnz .LBB0_1082
	s_ashr_i32 s0, s2, 31
	s_and_b32 s0, s0, s33
	s_add_i32 s3, s0, s2
	s_cmpk_gt_i32 s3, 0x3ff
	s_cbranch_scc1 .LBB0_1082
	v_lshrrev_b32_e32 v0, 3, v199
	s_waitcnt lgkmcnt(0)
	v_lshrrev_b32_e32 v1, 5, v199
	v_bfe_u32 v4, v199, 1, 3
	v_lshlrev_b32_e32 v5, 4, v199
	v_bfe_u32 v2, v199, 5, 1
	v_xor_b32_e32 v6, v5, v199
	v_lshlrev_b32_e32 v7, 11, v0
	s_movk_i32 s0, 0x70
	v_bitop3_b32 v1, v1, v4, 1 bitop3:0x6c
	v_and_or_b32 v64, v6, s0, v7
	v_lshlrev_b32_e32 v7, 4, v1
	v_bitop3_b32 v1, v2, v4, 2 bitop3:0x36
	v_lshrrev_b32_e32 v3, 1, v199
	v_lshlrev_b32_e32 v9, 4, v1
	v_bitop3_b32 v1, v2, v4, 4 bitop3:0x36
	v_mov_b32_e32 v65, 0
	v_and_b32_e32 v3, 0x1e0, v3
	v_lshlrev_b32_e32 v10, 4, v1
	v_bitop3_b32 v1, v2, v4, 6 bitop3:0x36
	s_waitcnt vmcnt(25)
	v_and_b32_e32 v138, 31, v199
	v_lshlrev_b32_e32 v2, 4, v1
	v_and_or_b32 v139, v0, 4, v3
	v_lshl_add_u64 v[0:1], s[14:15], 0, v[64:65]
	s_mov_b64 s[8:9], 0xb79f000
	s_add_u32 s10, s14, 0x5c4e000
	v_or_b32_e32 v6, v3, v138
	v_lshl_add_u64 v[66:67], v[0:1], 0, s[8:9]
	s_mov_b64 s[8:9], 0xba0000
	s_addc_u32 s11, s15, 0
	v_lshl_add_u32 v6, v6, 7, 0
	v_lshl_add_u32 v8, v138, 7, 0
	v_lshl_add_u64 v[68:69], v[0:1], 0, s[8:9]
	s_add_u32 s8, s14, 0x679f000
	v_add_u32_e32 v140, 0, v5
	v_mbcnt_lo_u32_b32 v0, -1, 0
	s_mov_b32 s7, 0
	v_cmp_eq_u32_e64 s[0:1], 0, v138
	s_addc_u32 s9, s15, 0
	v_add_u32_e32 v141, 0x4000, v140
	s_mov_b64 s[18:19], 0x10000
	v_add_u32_e32 v142, 0x1000, v140
	v_add_u32_e32 v143, 0x5000, v140
	s_mov_b64 s[20:21], 0x20000
	s_waitcnt vmcnt(24)
	v_add_u32_e32 v144, 0x2000, v140
	v_add_u32_e32 v145, 0x6000, v140
	s_mov_b64 s[22:23], 0x30000
	v_add_u32_e32 v146, 0x3000, v140
	v_add_u32_e32 v147, 0x7000, v140
	s_mov_b64 s[24:25], 0xb79f080
	s_mov_b64 s[26:27], 0xba0080
	v_add_u32_e32 v148, 0x8000, v140
	v_add_u32_e32 v149, 0xc000, v140
	s_mov_b64 s[28:29], 0xb7af080
	v_add_u32_e32 v150, 0x9000, v140
	s_mov_b64 s[30:31], 0xbb0080
	v_add_u32_e32 v151, 0xd000, v140
	s_mov_b64 s[34:35], 0xb7bf080
	s_waitcnt vmcnt(23)
	v_add_u32_e32 v152, 0xa000, v140
	s_mov_b64 s[36:37], 0xbc0080
	v_add_u32_e32 v153, 0xe000, v140
	s_mov_b64 s[38:39], 0xb7cf080
	v_add_u32_e32 v154, 0xb000, v140
	s_mov_b64 s[40:41], 0xbd0080
	v_add_u32_e32 v155, 0xf000, v140
	s_waitcnt vmcnt(22)
	v_add_u32_e32 v156, v6, v7
	v_add_u32_e32 v157, v8, v7
	v_add_u32_e32 v158, v6, v9
	v_add_u32_e32 v159, v8, v9
	s_waitcnt vmcnt(21)
	v_add_u32_e32 v160, v6, v10
	v_add_u32_e32 v161, v8, v10
	v_add_u32_e32 v162, v6, v2
	v_add_u32_e32 v163, v8, v2
	s_mov_b64 s[42:43], 0xb79f100
	s_mov_b64 s[44:45], 0xba0100
	s_mov_b64 s[46:47], 0xb7af100
	s_mov_b64 s[48:49], 0xbb0100
	s_mov_b64 s[50:51], 0xb7bf100
	s_mov_b64 s[52:53], 0xbc0100
	s_mov_b64 s[54:55], 0xb7cf100
	s_mov_b64 s[56:57], 0xbd0100
	s_add_i32 s70, 0, 0x12070
	s_waitcnt vmcnt(19)
	v_mbcnt_hi_u32_b32 v164, -1, v0
	s_mov_b32 s39, 0
	s_branch .LBB0_1046

.LBB0_1046:
	s_ashr_i32 s6, s3, 31
	s_lshr_b32 s6, s6, 26
	s_add_i32 s6, s3, s6
	s_ashr_i32 s58, s6, 6
	s_andn2_b32 s6, s6, 63
	s_sub_i32 s6, s3, s6
	s_ashr_i32 s59, s6, 31
	s_lshr_b32 s59, s59, 29
	s_add_i32 s59, s6, s59
	s_ashr_i32 s64, s59, 3
	s_and_b32 s59, s59, -8
	s_lshl_b32 s58, s58, 3
	s_sub_i32 s6, s6, s59
	s_add_i32 s6, s6, s58
	s_lshl_b32 s66, s6, 7
	s_ashr_i32 s67, s66, 31
	s_lshl_b32 s68, s64, 7
	s_lshl_b64 s[58:59], s[66:67], 11
	s_ashr_i32 s69, s68, 31
	s_cmp_eq_u32 s39, 1
	s_cbranch_scc1 .Lgk_pfhead_p11
	s_lshl_b32 s38, s66, 11
	s_add_u32 s18, s14, s38
	s_addc_u32 s19, s15, 0
	s_add_u32 s18, s18, 0xb79f000
	s_addc_u32 s19, s19, 0
	s_add_u32 s20, s18, 0x10000
	s_addc_u32 s21, s19, 0
	s_add_u32 s22, s20, 0x10000
	s_addc_u32 s23, s21, 0
	s_add_u32 s24, s22, 0x10000
	s_addc_u32 s25, s23, 0
	s_lshl_b32 s38, s68, 11
	s_add_u32 s26, s14, s38
	s_addc_u32 s27, s15, 0
	s_add_u32 s26, s26, 0xba0000
	s_addc_u32 s27, s27, 0
	s_add_u32 s28, s26, 0x10000
	s_addc_u32 s29, s27, 0
	s_add_u32 s30, s28, 0x10000
	s_addc_u32 s31, s29, 0
	s_add_u32 s34, s30, 0x10000
	s_addc_u32 s35, s31, 0
	v_readfirstlane_b32 s36, v140
	v_mov_b32_e32 v254, v64
	s_mov_b32 m0, s36
	s_nop 0
	global_load_lds_dwordx4 v254, s[18:19]
	s_add_u32 m0, m0, 0x1000
	s_nop 0
	global_load_lds_dwordx4 v254, s[20:21]
	s_add_u32 m0, m0, 0x1000
	s_nop 0
	global_load_lds_dwordx4 v254, s[22:23]
	s_add_u32 m0, m0, 0x1000
	s_nop 0
	global_load_lds_dwordx4 v254, s[24:25]
	s_add_u32 m0, m0, 0x1000
	s_nop 0
	global_load_lds_dwordx4 v254, s[26:27]
	s_add_u32 m0, m0, 0x1000
	s_nop 0
	global_load_lds_dwordx4 v254, s[28:29]
	s_add_u32 m0, m0, 0x1000
	s_nop 0
	global_load_lds_dwordx4 v254, s[30:31]
	s_add_u32 m0, m0, 0x1000
	s_nop 0
	global_load_lds_dwordx4 v254, s[34:35]
	v_add_u32_e32 v254, 0x80, v254
	s_add_u32 m0, s36, 0x8000
	s_nop 0
	global_load_lds_dwordx4 v254, s[18:19]
	s_add_u32 m0, m0, 0x1000
	s_nop 0
	global_load_lds_dwordx4 v254, s[20:21]
	s_add_u32 m0, m0, 0x1000
	s_nop 0
	global_load_lds_dwordx4 v254, s[22:23]
	s_add_u32 m0, m0, 0x1000
	s_nop 0
	global_load_lds_dwordx4 v254, s[24:25]
	s_add_u32 m0, m0, 0x1000
	s_nop 0
	global_load_lds_dwordx4 v254, s[26:27]
	s_add_u32 m0, m0, 0x1000
	s_nop 0
	global_load_lds_dwordx4 v254, s[28:29]
	s_add_u32 m0, m0, 0x1000
	s_nop 0
	global_load_lds_dwordx4 v254, s[30:31]
	s_add_u32 m0, m0, 0x1000
	s_nop 0
	global_load_lds_dwordx4 v254, s[34:35]
	v_add_u32_e32 v254, 0x80, v254

.Lgk_loop_p11:
	s_waitcnt vmcnt(8)
	s_barrier
	ds_read_b128 v[70:73], v156
	ds_read_b128 v[74:77], v157 offset:16384
	ds_read_b128 v[78:81], v157 offset:20480
	ds_read_b128 v[82:85], v157 offset:24576
	ds_read_b128 v[86:89], v157 offset:28672
	ds_read_b128 v[90:93], v158
	ds_read_b128 v[94:97], v159 offset:16384
	ds_read_b128 v[98:101], v159 offset:20480
	ds_read_b128 v[102:105], v159 offset:24576
	ds_read_b128 v[106:109], v159 offset:28672
	ds_read_b128 v[110:113], v160
	ds_read_b128 v[202:205], v161 offset:16384
	ds_read_b128 v[206:209], v161 offset:20480
	ds_read_b128 v[210:213], v161 offset:24576
	ds_read_b128 v[214:217], v161 offset:28672
	ds_read_b128 v[218:221], v162
	ds_read_b128 v[222:225], v163 offset:16384
	ds_read_b128 v[226:229], v163 offset:20480
	ds_read_b128 v[230:233], v163 offset:24576
	ds_read_b128 v[234:237], v163 offset:28672
	s_waitcnt lgkmcnt(0)
	s_barrier
	s_mov_b32 m0, s36
	s_setprio 1
	v_mfma_f32_32x32x16_bf16 v[48:63], v[70:73], v[74:77], v[48:63]
	v_mfma_f32_32x32x16_bf16 v[32:47], v[70:73], v[78:81], v[32:47]
	global_load_lds_dwordx4 v254, s[18:19]
	s_add_u32 m0, m0, 0x1000
	v_mfma_f32_32x32x16_bf16 v[16:31], v[70:73], v[82:85], v[16:31]
	v_mfma_f32_32x32x16_bf16 v[0:15], v[70:73], v[86:89], v[0:15]
	global_load_lds_dwordx4 v254, s[20:21]
	s_add_u32 m0, m0, 0x1000
	v_mfma_f32_32x32x16_bf16 v[48:63], v[90:93], v[94:97], v[48:63]
	v_mfma_f32_32x32x16_bf16 v[32:47], v[90:93], v[98:101], v[32:47]
	global_load_lds_dwordx4 v254, s[22:23]
	s_add_u32 m0, m0, 0x1000
	v_mfma_f32_32x32x16_bf16 v[16:31], v[90:93], v[102:105], v[16:31]
	v_mfma_f32_32x32x16_bf16 v[0:15], v[90:93], v[106:109], v[0:15]
	global_load_lds_dwordx4 v254, s[24:25]
	s_add_u32 m0, m0, 0x1000
	v_mfma_f32_32x32x16_bf16 v[48:63], v[110:113], v[202:205], v[48:63]
	v_mfma_f32_32x32x16_bf16 v[32:47], v[110:113], v[206:209], v[32:47]
	global_load_lds_dwordx4 v254, s[26:27]
	s_add_u32 m0, m0, 0x1000
	v_mfma_f32_32x32x16_bf16 v[16:31], v[110:113], v[210:213], v[16:31]
	v_mfma_f32_32x32x16_bf16 v[0:15], v[110:113], v[214:217], v[0:15]
	global_load_lds_dwordx4 v254, s[28:29]
	s_add_u32 m0, m0, 0x1000
	v_mfma_f32_32x32x16_bf16 v[48:63], v[218:221], v[222:225], v[48:63]
	v_mfma_f32_32x32x16_bf16 v[32:47], v[218:221], v[226:229], v[32:47]
	global_load_lds_dwordx4 v254, s[30:31]
	s_add_u32 m0, m0, 0x1000
	v_mfma_f32_32x32x16_bf16 v[16:31], v[218:221], v[230:233], v[16:31]
	v_mfma_f32_32x32x16_bf16 v[0:15], v[218:221], v[234:237], v[0:15]
	global_load_lds_dwordx4 v254, s[34:35]
	s_setprio 0
	v_add_u32_e32 v254, 0x80, v254
	s_waitcnt vmcnt(8)
	s_barrier
	ds_read_b128 v[70:73], v156 offset:32768
	ds_read_b128 v[74:77], v157 offset:49152
	ds_read_b128 v[78:81], v157 offset:53248
	ds_read_b128 v[82:85], v157 offset:57344
	ds_read_b128 v[86:89], v157 offset:61440
	ds_read_b128 v[90:93], v158 offset:32768
	ds_read_b128 v[94:97], v159 offset:49152
	ds_read_b128 v[98:101], v159 offset:53248
	ds_read_b128 v[102:105], v159 offset:57344
	ds_read_b128 v[106:109], v159 offset:61440
	ds_read_b128 v[110:113], v160 offset:32768
	ds_read_b128 v[202:205], v161 offset:49152
	ds_read_b128 v[206:209], v161 offset:53248
	ds_read_b128 v[210:213], v161 offset:57344
	ds_read_b128 v[214:217], v161 offset:61440
	ds_read_b128 v[218:221], v162 offset:32768
	ds_read_b128 v[222:225], v163 offset:49152
	ds_read_b128 v[226:229], v163 offset:53248
	ds_read_b128 v[230:233], v163 offset:57344
	ds_read_b128 v[234:237], v163 offset:61440
	s_waitcnt lgkmcnt(0)
	s_barrier
	s_add_u32 m0, s36, 0x8000
	s_setprio 1
	v_mfma_f32_32x32x16_bf16 v[48:63], v[70:73], v[74:77], v[48:63]
	v_mfma_f32_32x32x16_bf16 v[32:47], v[70:73], v[78:81], v[32:47]
	global_load_lds_dwordx4 v254, s[18:19]
	s_add_u32 m0, m0, 0x1000
	v_mfma_f32_32x32x16_bf16 v[16:31], v[70:73], v[82:85], v[16:31]
	v_mfma_f32_32x32x16_bf16 v[0:15], v[70:73], v[86:89], v[0:15]
	global_load_lds_dwordx4 v254, s[20:21]
	s_add_u32 m0, m0, 0x1000
	v_mfma_f32_32x32x16_bf16 v[48:63], v[90:93], v[94:97], v[48:63]
	v_mfma_f32_32x32x16_bf16 v[32:47], v[90:93], v[98:101], v[32:47]
	global_load_lds_dwordx4 v254, s[22:23]
	s_add_u32 m0, m0, 0x1000
	v_mfma_f32_32x32x16_bf16 v[16:31], v[90:93], v[102:105], v[16:31]
	v_mfma_f32_32x32x16_bf16 v[0:15], v[90:93], v[106:109], v[0:15]
	global_load_lds_dwordx4 v254, s[24:25]
	s_add_u32 m0, m0, 0x1000
	v_mfma_f32_32x32x16_bf16 v[48:63], v[110:113], v[202:205], v[48:63]
	v_mfma_f32_32x32x16_bf16 v[32:47], v[110:113], v[206:209], v[32:47]
	global_load_lds_dwordx4 v254, s[26:27]
	s_add_u32 m0, m0, 0x1000
	v_mfma_f32_32x32x16_bf16 v[16:31], v[110:113], v[210:213], v[16:31]
	v_mfma_f32_32x32x16_bf16 v[0:15], v[110:113], v[214:217], v[0:15]
	global_load_lds_dwordx4 v254, s[28:29]
	s_add_u32 m0, m0, 0x1000
	v_mfma_f32_32x32x16_bf16 v[48:63], v[218:221], v[222:225], v[48:63]
	v_mfma_f32_32x32x16_bf16 v[32:47], v[218:221], v[226:229], v[32:47]
	global_load_lds_dwordx4 v254, s[30:31]
	s_add_u32 m0, m0, 0x1000
	v_mfma_f32_32x32x16_bf16 v[16:31], v[218:221], v[230:233], v[16:31]
	v_mfma_f32_32x32x16_bf16 v[0:15], v[218:221], v[234:237], v[0:15]
	global_load_lds_dwordx4 v254, s[34:35]
	s_setprio 0
	v_add_u32_e32 v254, 0x80, v254
	s_sub_u32 s37, s37, 1
	s_cmp_lg_u32 s37, 0
	s_cbranch_scc1 .Lgk_loop_p11
	s_add_u32 s40, s3, s33
	s_cmp_gt_u32 s40, 0x3ff
	s_cbranch_scc1 .Lgk_tailplain_p11
.LBB0_1046_pf_p11:
	s_ashr_i32 s41, s40, 31
	s_lshr_b32 s41, s41, 26
	s_add_i32 s41, s40, s41
	s_ashr_i32 s42, s41, 6
	s_andn2_b32 s41, s41, 63
	s_sub_i32 s41, s40, s41
	s_ashr_i32 s43, s41, 31
	s_lshr_b32 s43, s43, 29
	s_add_i32 s43, s41, s43
	s_ashr_i32 s46, s43, 3
	s_and_b32 s43, s43, -8
	s_lshl_b32 s42, s42, 3
	s_sub_i32 s41, s41, s43
	s_add_i32 s41, s41, s42
	s_lshl_b32 s44, s41, 7
	s_ashr_i32 s45, s44, 31
	s_lshl_b32 s47, s46, 7
	s_lshl_b64 s[42:43], s[44:45], 11
	s_ashr_i32 s48, s47, 31
	s_lshl_b32 s38, s44, 11
	s_add_u32 s18, s14, s38
	s_addc_u32 s19, s15, 0
	s_add_u32 s18, s18, 0xb79f000
	s_addc_u32 s19, s19, 0
	s_add_u32 s20, s18, 0x10000
	s_addc_u32 s21, s19, 0
	s_add_u32 s22, s20, 0x10000
	s_addc_u32 s23, s21, 0
	s_add_u32 s24, s22, 0x10000
	s_addc_u32 s25, s23, 0
	s_lshl_b32 s38, s47, 11
	s_add_u32 s26, s14, s38
	s_addc_u32 s27, s15, 0
	s_add_u32 s26, s26, 0xba0000
	s_addc_u32 s27, s27, 0
	s_add_u32 s28, s26, 0x10000
	s_addc_u32 s29, s27, 0
	s_add_u32 s30, s28, 0x10000
	s_addc_u32 s31, s29, 0
	s_add_u32 s34, s30, 0x10000
	s_addc_u32 s35, s31, 0
	v_mov_b32_e32 v254, v64
	s_mov_b32 s39, 1
	s_waitcnt vmcnt(8)
	s_barrier
	ds_read_b128 v[70:73], v156
	ds_read_b128 v[74:77], v157 offset:16384
	ds_read_b128 v[78:81], v157 offset:20480
	ds_read_b128 v[82:85], v157 offset:24576
	ds_read_b128 v[86:89], v157 offset:28672
	ds_read_b128 v[90:93], v158
	ds_read_b128 v[94:97], v159 offset:16384
	ds_read_b128 v[98:101], v159 offset:20480
	ds_read_b128 v[102:105], v159 offset:24576
	ds_read_b128 v[106:109], v159 offset:28672
	ds_read_b128 v[110:113], v160
	ds_read_b128 v[202:205], v161 offset:16384
	ds_read_b128 v[206:209], v161 offset:20480
	ds_read_b128 v[210:213], v161 offset:24576
	ds_read_b128 v[214:217], v161 offset:28672
	ds_read_b128 v[218:221], v162
	ds_read_b128 v[222:225], v163 offset:16384
	ds_read_b128 v[226:229], v163 offset:20480
	ds_read_b128 v[230:233], v163 offset:24576
	ds_read_b128 v[234:237], v163 offset:28672
	s_waitcnt lgkmcnt(0)
	s_barrier
	s_mov_b32 m0, s36
	s_setprio 1
	v_mfma_f32_32x32x16_bf16 v[48:63], v[70:73], v[74:77], v[48:63]
	v_mfma_f32_32x32x16_bf16 v[32:47], v[70:73], v[78:81], v[32:47]
	global_load_lds_dwordx4 v254, s[18:19]
	s_add_u32 m0, m0, 0x1000
	v_mfma_f32_32x32x16_bf16 v[16:31], v[70:73], v[82:85], v[16:31]
	v_mfma_f32_32x32x16_bf16 v[0:15], v[70:73], v[86:89], v[0:15]
	global_load_lds_dwordx4 v254, s[20:21]
	s_add_u32 m0, m0, 0x1000
	v_mfma_f32_32x32x16_bf16 v[48:63], v[90:93], v[94:97], v[48:63]
	v_mfma_f32_32x32x16_bf16 v[32:47], v[90:93], v[98:101], v[32:47]
	global_load_lds_dwordx4 v254, s[22:23]
	s_add_u32 m0, m0, 0x1000
	v_mfma_f32_32x32x16_bf16 v[16:31], v[90:93], v[102:105], v[16:31]
	v_mfma_f32_32x32x16_bf16 v[0:15], v[90:93], v[106:109], v[0:15]
	global_load_lds_dwordx4 v254, s[24:25]
	s_add_u32 m0, m0, 0x1000
	v_mfma_f32_32x32x16_bf16 v[48:63], v[110:113], v[202:205], v[48:63]
	v_mfma_f32_32x32x16_bf16 v[32:47], v[110:113], v[206:209], v[32:47]
	global_load_lds_dwordx4 v254, s[26:27]
	s_add_u32 m0, m0, 0x1000
	v_mfma_f32_32x32x16_bf16 v[16:31], v[110:113], v[210:213], v[16:31]
	v_mfma_f32_32x32x16_bf16 v[0:15], v[110:113], v[214:217], v[0:15]
	global_load_lds_dwordx4 v254, s[28:29]
	s_add_u32 m0, m0, 0x1000
	v_mfma_f32_32x32x16_bf16 v[48:63], v[218:221], v[222:225], v[48:63]
	v_mfma_f32_32x32x16_bf16 v[32:47], v[218:221], v[226:229], v[32:47]
	global_load_lds_dwordx4 v254, s[30:31]
	s_add_u32 m0, m0, 0x1000
	v_mfma_f32_32x32x16_bf16 v[16:31], v[218:221], v[230:233], v[16:31]
	v_mfma_f32_32x32x16_bf16 v[0:15], v[218:221], v[234:237], v[0:15]
	global_load_lds_dwordx4 v254, s[34:35]
	s_setprio 0
	v_add_u32_e32 v254, 0x80, v254
	s_waitcnt vmcnt(8)
	s_barrier
	ds_read_b128 v[70:73], v156 offset:32768
	ds_read_b128 v[74:77], v157 offset:49152
	ds_read_b128 v[78:81], v157 offset:53248
	ds_read_b128 v[82:85], v157 offset:57344
	ds_read_b128 v[86:89], v157 offset:61440
	ds_read_b128 v[90:93], v158 offset:32768
	ds_read_b128 v[94:97], v159 offset:49152
	ds_read_b128 v[98:101], v159 offset:53248
	ds_read_b128 v[102:105], v159 offset:57344
	ds_read_b128 v[106:109], v159 offset:61440
	ds_read_b128 v[110:113], v160 offset:32768
	ds_read_b128 v[202:205], v161 offset:49152
	ds_read_b128 v[206:209], v161 offset:53248
	ds_read_b128 v[210:213], v161 offset:57344
	ds_read_b128 v[214:217], v161 offset:61440
	ds_read_b128 v[218:221], v162 offset:32768
	ds_read_b128 v[222:225], v163 offset:49152
	ds_read_b128 v[226:229], v163 offset:53248
	ds_read_b128 v[230:233], v163 offset:57344
	ds_read_b128 v[234:237], v163 offset:61440
	s_waitcnt lgkmcnt(0)
	s_barrier
	s_add_u32 m0, s36, 0x8000
	s_setprio 1
	v_mfma_f32_32x32x16_bf16 v[48:63], v[70:73], v[74:77], v[48:63]
	v_mfma_f32_32x32x16_bf16 v[32:47], v[70:73], v[78:81], v[32:47]
	global_load_lds_dwordx4 v254, s[18:19]
	s_add_u32 m0, m0, 0x1000
	v_mfma_f32_32x32x16_bf16 v[16:31], v[70:73], v[82:85], v[16:31]
	v_mfma_f32_32x32x16_bf16 v[0:15], v[70:73], v[86:89], v[0:15]
	global_load_lds_dwordx4 v254, s[20:21]
	s_add_u32 m0, m0, 0x1000
	v_mfma_f32_32x32x16_bf16 v[48:63], v[90:93], v[94:97], v[48:63]
	v_mfma_f32_32x32x16_bf16 v[32:47], v[90:93], v[98:101], v[32:47]
	global_load_lds_dwordx4 v254, s[22:23]
	s_add_u32 m0, m0, 0x1000
	v_mfma_f32_32x32x16_bf16 v[16:31], v[90:93], v[102:105], v[16:31]
	v_mfma_f32_32x32x16_bf16 v[0:15], v[90:93], v[106:109], v[0:15]
	global_load_lds_dwordx4 v254, s[24:25]
	s_add_u32 m0, m0, 0x1000
	v_mfma_f32_32x32x16_bf16 v[48:63], v[110:113], v[202:205], v[48:63]
	v_mfma_f32_32x32x16_bf16 v[32:47], v[110:113], v[206:209], v[32:47]
	global_load_lds_dwordx4 v254, s[26:27]
	s_add_u32 m0, m0, 0x1000
	v_mfma_f32_32x32x16_bf16 v[16:31], v[110:113], v[210:213], v[16:31]
	v_mfma_f32_32x32x16_bf16 v[0:15], v[110:113], v[214:217], v[0:15]
	global_load_lds_dwordx4 v254, s[28:29]
	s_add_u32 m0, m0, 0x1000
	v_mfma_f32_32x32x16_bf16 v[48:63], v[218:221], v[222:225], v[48:63]
	v_mfma_f32_32x32x16_bf16 v[32:47], v[218:221], v[226:229], v[32:47]
	global_load_lds_dwordx4 v254, s[30:31]
	s_add_u32 m0, m0, 0x1000
	v_mfma_f32_32x32x16_bf16 v[16:31], v[218:221], v[230:233], v[16:31]
	v_mfma_f32_32x32x16_bf16 v[0:15], v[218:221], v[234:237], v[0:15]
	global_load_lds_dwordx4 v254, s[34:35]
	s_setprio 0
	v_add_u32_e32 v254, 0x80, v254
	s_branch .LBB0_1050
.Lgk_tailplain_p11:
	s_mov_b32 s39, 0
	s_waitcnt vmcnt(8)
	s_barrier
	ds_read_b128 v[70:73], v156
	ds_read_b128 v[74:77], v157 offset:16384
	ds_read_b128 v[78:81], v157 offset:20480
	ds_read_b128 v[82:85], v157 offset:24576
	ds_read_b128 v[86:89], v157 offset:28672
	ds_read_b128 v[90:93], v158
	ds_read_b128 v[94:97], v159 offset:16384
	ds_read_b128 v[98:101], v159 offset:20480
	ds_read_b128 v[102:105], v159 offset:24576
	ds_read_b128 v[106:109], v159 offset:28672
	ds_read_b128 v[110:113], v160
	ds_read_b128 v[202:205], v161 offset:16384
	ds_read_b128 v[206:209], v161 offset:20480
	ds_read_b128 v[210:213], v161 offset:24576
	ds_read_b128 v[214:217], v161 offset:28672
	ds_read_b128 v[218:221], v162
	ds_read_b128 v[222:225], v163 offset:16384
	ds_read_b128 v[226:229], v163 offset:20480
	ds_read_b128 v[230:233], v163 offset:24576
	ds_read_b128 v[234:237], v163 offset:28672
	s_waitcnt lgkmcnt(0)
	s_barrier
	s_setprio 1
	v_mfma_f32_32x32x16_bf16 v[48:63], v[70:73], v[74:77], v[48:63]
	v_mfma_f32_32x32x16_bf16 v[32:47], v[70:73], v[78:81], v[32:47]
	v_mfma_f32_32x32x16_bf16 v[16:31], v[70:73], v[82:85], v[16:31]
	v_mfma_f32_32x32x16_bf16 v[0:15], v[70:73], v[86:89], v[0:15]
	v_mfma_f32_32x32x16_bf16 v[48:63], v[90:93], v[94:97], v[48:63]
	v_mfma_f32_32x32x16_bf16 v[32:47], v[90:93], v[98:101], v[32:47]
	v_mfma_f32_32x32x16_bf16 v[16:31], v[90:93], v[102:105], v[16:31]
	v_mfma_f32_32x32x16_bf16 v[0:15], v[90:93], v[106:109], v[0:15]
	v_mfma_f32_32x32x16_bf16 v[48:63], v[110:113], v[202:205], v[48:63]
	v_mfma_f32_32x32x16_bf16 v[32:47], v[110:113], v[206:209], v[32:47]
	v_mfma_f32_32x32x16_bf16 v[16:31], v[110:113], v[210:213], v[16:31]
	v_mfma_f32_32x32x16_bf16 v[0:15], v[110:113], v[214:217], v[0:15]
	v_mfma_f32_32x32x16_bf16 v[48:63], v[218:221], v[222:225], v[48:63]
	v_mfma_f32_32x32x16_bf16 v[32:47], v[218:221], v[226:229], v[32:47]
	v_mfma_f32_32x32x16_bf16 v[16:31], v[218:221], v[230:233], v[16:31]
	v_mfma_f32_32x32x16_bf16 v[0:15], v[218:221], v[234:237], v[0:15]
	s_setprio 0
	s_waitcnt vmcnt(0)
	s_barrier
	ds_read_b128 v[70:73], v156 offset:32768
	ds_read_b128 v[74:77], v157 offset:49152
	ds_read_b128 v[78:81], v157 offset:53248
	ds_read_b128 v[82:85], v157 offset:57344
	ds_read_b128 v[86:89], v157 offset:61440
	ds_read_b128 v[90:93], v158 offset:32768
	ds_read_b128 v[94:97], v159 offset:49152
	ds_read_b128 v[98:101], v159 offset:53248
	ds_read_b128 v[102:105], v159 offset:57344
	ds_read_b128 v[106:109], v159 offset:61440
	ds_read_b128 v[110:113], v160 offset:32768
	ds_read_b128 v[202:205], v161 offset:49152
	ds_read_b128 v[206:209], v161 offset:53248
	ds_read_b128 v[210:213], v161 offset:57344
	ds_read_b128 v[214:217], v161 offset:61440
	ds_read_b128 v[218:221], v162 offset:32768
	ds_read_b128 v[222:225], v163 offset:49152
	ds_read_b128 v[226:229], v163 offset:53248
	ds_read_b128 v[230:233], v163 offset:57344
	ds_read_b128 v[234:237], v163 offset:61440
	s_waitcnt lgkmcnt(0)
	s_barrier
	s_setprio 1
	v_mfma_f32_32x32x16_bf16 v[48:63], v[70:73], v[74:77], v[48:63]
	v_mfma_f32_32x32x16_bf16 v[32:47], v[70:73], v[78:81], v[32:47]
	v_mfma_f32_32x32x16_bf16 v[16:31], v[70:73], v[82:85], v[16:31]
	v_mfma_f32_32x32x16_bf16 v[0:15], v[70:73], v[86:89], v[0:15]
	v_mfma_f32_32x32x16_bf16 v[48:63], v[90:93], v[94:97], v[48:63]
	v_mfma_f32_32x32x16_bf16 v[32:47], v[90:93], v[98:101], v[32:47]
	v_mfma_f32_32x32x16_bf16 v[16:31], v[90:93], v[102:105], v[16:31]
	v_mfma_f32_32x32x16_bf16 v[0:15], v[90:93], v[106:109], v[0:15]
	v_mfma_f32_32x32x16_bf16 v[48:63], v[110:113], v[202:205], v[48:63]
	v_mfma_f32_32x32x16_bf16 v[32:47], v[110:113], v[206:209], v[32:47]
	v_mfma_f32_32x32x16_bf16 v[16:31], v[110:113], v[210:213], v[16:31]
	v_mfma_f32_32x32x16_bf16 v[0:15], v[110:113], v[214:217], v[0:15]
	v_mfma_f32_32x32x16_bf16 v[48:63], v[218:221], v[222:225], v[48:63]
	v_mfma_f32_32x32x16_bf16 v[32:47], v[218:221], v[226:229], v[32:47]
	v_mfma_f32_32x32x16_bf16 v[16:31], v[218:221], v[230:233], v[16:31]
	v_mfma_f32_32x32x16_bf16 v[0:15], v[218:221], v[234:237], v[0:15]
	s_setprio 0
	s_branch .LBB0_1050
.LBB0_1050:
	s_add_i32 s58, s66, 0xffffe000
	s_lshr_b32 s58, s58, 12
	s_mulk_i32 s58, 0x1800
	v_mov_b32_e32 v70, s70
	s_addk_i32 s58, 0x6000
	ds_read_b64 v[70:71], v70
	s_cmp_gt_i32 s6, 63
	s_cselect_b32 s6, s58, 0x4800
	s_lshl_b64 s[58:59], s[6:7], 2
	s_add_u32 s6, s14, s58
	s_addc_u32 s65, s15, s59
	s_waitcnt lgkmcnt(0)
	v_readfirstlane_b32 s58, v70
	v_readfirstlane_b32 s59, v71
	s_add_u32 s60, s58, 0x1000
	s_addc_u32 s61, s59, 0
	s_lshl_b32 s58, s64, 14
	s_add_i32 s58, s58, 0x60000
	s_ashr_i32 s59, s58, 31
	s_lshl_b64 s[58:59], s[58:59], 2
	s_add_u32 s58, s10, s58
	s_addc_u32 s59, s11, s59
	s_add_u32 s62, s6, 0x5ba2000
	v_or_b32_e32 v102, s68, v138
	v_add_u32_e32 v70, s66, v139
	s_addc_u32 s63, s65, 0
	v_lshlrev_b32_e32 v188, 10, v70
	v_ashrrev_i32_e32 v103, 31, v102
	s_add_u32 s64, s6, 0x5ba4000
	v_lshlrev_b64 v[72:73], 2, v[102:103]
	v_or_b32_e32 v186, 0x400, v188
	v_or_b32_e32 v185, 0x4400, v188
	v_or_b32_e32 v189, 0x4c00, v188
	v_or_b32_e32 v193, 0x6c00, v188
	s_addc_u32 s65, s65, 0
	v_lshl_add_u64 v[74:75], s[62:63], 0, v[72:73]
	v_add_u32_e32 v132, v188, v102
	v_add_u32_e32 v134, v186, v102
	v_or_b32_e32 v184, 0x800, v188
	v_or_b32_e32 v183, 0xc00, v188
	v_or_b32_e32 v181, 0x2000, v188
	v_or_b32_e32 v179, 0x2400, v188
	v_or_b32_e32 v71, 0x2800, v188
	v_or_b32_e32 v180, 0x2c00, v188
	v_or_b32_e32 v182, 0x4000, v188
	v_add_u32_e32 v112, v185, v102
	v_or_b32_e32 v187, 0x4800, v188
	v_add_u32_e32 v118, v189, v102
	v_or_b32_e32 v190, 0x6000, v188
	v_or_b32_e32 v191, 0x6400, v188
	v_or_b32_e32 v192, 0x6800, v188
	v_add_u32_e32 v128, v193, v102
	global_load_dword v194, v[74:75], off
	v_lshl_add_u64 v[74:75], s[60:61], 0, v[72:73]
	v_lshl_add_u64 v[72:73], s[64:65], 0, v[72:73]
	v_ashrrev_i32_e32 v135, 31, v134
	v_add_u32_e32 v136, v184, v102
	v_add_u32_e32 v130, v183, v102
	v_add_u32_e32 v122, v181, v102
	v_add_u32_e32 v114, v179, v102
	v_add_u32_e32 v106, v71, v102
	v_add_u32_e32 v108, v180, v102
	v_add_u32_e32 v110, v182, v102
	v_ashrrev_i32_e32 v113, 31, v112
	v_add_u32_e32 v116, v187, v102
	v_ashrrev_i32_e32 v119, 31, v118
	v_add_u32_e32 v120, v190, v102
	v_add_u32_e32 v124, v191, v102
	v_add_u32_e32 v126, v192, v102
	v_ashrrev_i32_e32 v129, 31, v128
	v_ashrrev_i32_e32 v133, 31, v132
	global_load_dword v196, v[72:73], off
	v_lshl_add_u64 v[88:89], v[134:135], 2, s[12:13]
	v_ashrrev_i32_e32 v137, 31, v136
	v_ashrrev_i32_e32 v131, 31, v130
	v_ashrrev_i32_e32 v123, 31, v122
	v_ashrrev_i32_e32 v115, 31, v114
	v_ashrrev_i32_e32 v107, 31, v106
	v_ashrrev_i32_e32 v109, 31, v108
	v_ashrrev_i32_e32 v111, 31, v110
	v_lshl_add_u64 v[86:87], v[112:113], 2, s[12:13]
	v_ashrrev_i32_e32 v117, 31, v116
	v_lshl_add_u64 v[92:93], v[118:119], 2, s[12:13]
	v_ashrrev_i32_e32 v121, 31, v120
	v_ashrrev_i32_e32 v125, 31, v124
	v_ashrrev_i32_e32 v127, 31, v126
	v_lshl_add_u64 v[100:101], v[128:129], 2, s[12:13]
	v_lshl_add_u64 v[104:105], v[132:133], 2, s[12:13]
	global_load_dword v195, v[74:75], off
	v_lshl_add_u64 v[84:85], v[136:137], 2, s[12:13]
	v_lshl_add_u64 v[82:83], v[130:131], 2, s[12:13]
	v_lshl_add_u64 v[78:79], v[122:123], 2, s[12:13]
	v_lshl_add_u64 v[72:73], v[114:115], 2, s[12:13]
	v_lshl_add_u64 v[74:75], v[106:107], 2, s[12:13]
	v_lshl_add_u64 v[76:77], v[108:109], 2, s[12:13]
	v_lshl_add_u64 v[80:81], v[110:111], 2, s[12:13]
	global_load_dword v178, v[88:89], off
	global_load_dword v177, v[84:85], off
	global_load_dword v176, v[82:83], off
	global_load_dword v175, v[78:79], off
	global_load_dword v174, v[72:73], off
	global_load_dword v173, v[74:75], off
	global_load_dword v172, v[76:77], off
	global_load_dword v171, v[80:81], off
	v_lshl_add_u64 v[90:91], v[116:117], 2, s[12:13]
	global_load_dword v170, v[86:87], off
	global_load_dword v168, v[90:91], off
	v_lshl_add_u64 v[94:95], v[120:121], 2, s[12:13]
	v_lshl_add_u64 v[96:97], v[124:125], 2, s[12:13]
	v_lshl_add_u64 v[98:99], v[126:127], 2, s[12:13]
	global_load_dword v169, v[92:93], off
	global_load_dword v167, v[94:95], off
	global_load_dword v166, v[96:97], off
	global_load_dword v165, v[98:99], off
	global_load_dword v103, v[100:101], off
	global_load_dword v197, v[104:105], off
	v_lshl_add_u64 v[106:107], v[106:107], 1, s[8:9]
	s_waitcnt vmcnt(0)
	v_add_f32_e32 v196, 1.0, v196
	v_mul_f32_e32 v195, v195, v196
	v_fmac_f32_e32 v178, v49, v194
	v_fmac_f32_e32 v177, v50, v194
	v_fmac_f32_e32 v176, v51, v194
	v_fmac_f32_e32 v175, v52, v194
	v_fmac_f32_e32 v174, v53, v194
	v_fmac_f32_e32 v173, v54, v194
	v_fmac_f32_e32 v172, v55, v194
	v_fmac_f32_e32 v171, v56, v194
	v_fmac_f32_e32 v170, v57, v194
	v_fmac_f32_e32 v168, v58, v194
	v_fmac_f32_e32 v169, v59, v194
	v_fmac_f32_e32 v167, v60, v194
	v_fmac_f32_e32 v166, v61, v194
	v_fmac_f32_e32 v165, v62, v194
	v_fmac_f32_e32 v103, v63, v194
	v_fmac_f32_e32 v197, v48, v194
	v_mul_f32_e32 v48, v195, v197
	v_cvt_pk_bf16_f32 v58, v48, s0
	v_or_b32_e32 v48, 32, v102
	v_ashrrev_i32_e32 v49, 31, v48
	v_lshlrev_b64 v[52:53], 2, v[48:49]
	global_store_dword v[88:89], v178, off sc1
	global_store_dword v[84:85], v177, off sc1
	global_store_dword v[82:83], v176, off sc1
	global_store_dword v[78:79], v175, off sc1
	global_store_dword v[72:73], v174, off sc1
	global_store_dword v[74:75], v173, off sc1
	global_store_dword v[76:77], v172, off sc1
	global_store_dword v[80:81], v171, off sc1
	global_store_dword v[86:87], v170, off sc1
	global_store_dword v[90:91], v168, off sc1
	global_store_dword v[92:93], v169, off sc1
	global_store_dword v[94:95], v167, off sc1
	global_store_dword v[96:97], v166, off sc1
	global_store_dword v[98:99], v165, off sc1
	global_store_dword v[100:101], v103, off sc1
	global_store_dword v[104:105], v197, off sc1
	v_lshl_add_u64 v[50:51], v[132:133], 1, s[8:9]
	v_lshl_add_u64 v[56:57], s[64:65], 0, v[52:53]
	global_load_dword v196, v[104:105], off offset:128
	v_lshl_add_u64 v[54:55], s[60:61], 0, v[52:53]
	global_load_dword v132, v[56:57], off
	global_load_dword v133, v[54:55], off
	v_mul_f32_e32 v49, v195, v178
	global_store_short v[50:51], v58, off sc1
	v_lshl_add_u64 v[50:51], s[62:63], 0, v[52:53]
	global_load_dword v194, v[50:51], off
	v_cvt_pk_bf16_f32 v49, v49, s0
	v_lshl_add_u64 v[50:51], v[134:135], 1, s[8:9]
	global_store_short v[50:51], v49, off sc1
	v_mul_f32_e32 v49, v195, v177
	v_cvt_pk_bf16_f32 v49, v49, s0
	v_lshl_add_u64 v[50:51], v[136:137], 1, s[8:9]
	global_store_short v[50:51], v49, off sc1
	v_mul_f32_e32 v49, v195, v176
	v_cvt_pk_bf16_f32 v49, v49, s0
	v_lshl_add_u64 v[50:51], v[130:131], 1, s[8:9]
	global_store_short v[50:51], v49, off sc1
	v_mul_f32_e32 v49, v195, v175
	v_cvt_pk_bf16_f32 v49, v49, s0
	v_lshl_add_u64 v[50:51], v[122:123], 1, s[8:9]
	global_store_short v[50:51], v49, off sc1
	v_mul_f32_e32 v49, v195, v174
	v_cvt_pk_bf16_f32 v49, v49, s0
	v_lshl_add_u64 v[50:51], v[114:115], 1, s[8:9]
	global_store_short v[50:51], v49, off sc1
	v_mul_f32_e32 v49, v195, v173
	global_load_dword v62, v[84:85], off offset:128
	global_load_dword v60, v[78:79], off offset:128
	global_load_dword v59, v[72:73], off offset:128
	global_load_dword v58, v[74:75], off offset:128
	global_load_dword v56, v[80:81], off offset:128
	global_load_dword v57, v[76:77], off offset:128
	global_load_dword v55, v[86:87], off offset:128
	global_load_dword v61, v[82:83], off offset:128
	global_load_dword v54, v[90:91], off offset:128
	global_load_dword v53, v[92:93], off offset:128
	global_load_dword v52, v[94:95], off offset:128
	global_load_dword v51, v[96:97], off offset:128
	global_load_dword v50, v[98:99], off offset:128
	v_cvt_pk_bf16_f32 v63, v49, s0
	global_load_dword v49, v[100:101], off offset:128
	s_waitcnt vmcnt(19)
	v_fmac_f32_e32 v196, v32, v194
	global_store_short v[106:107], v63, off sc1
	global_load_dword v63, v[88:89], off offset:128
	v_mul_f32_e32 v106, v195, v172
	v_cvt_pk_bf16_f32 v114, v106, s0
	v_lshl_add_u64 v[106:107], v[108:109], 1, s[8:9]
	global_store_short v[106:107], v114, off sc1
	v_mul_f32_e32 v106, v195, v171
	v_cvt_pk_bf16_f32 v108, v106, s0
	v_lshl_add_u64 v[106:107], v[110:111], 1, s[8:9]
	global_store_short v[106:107], v108, off sc1
	v_mul_f32_e32 v106, v195, v170
	v_cvt_pk_bf16_f32 v108, v106, s0
	v_lshl_add_u64 v[106:107], v[112:113], 1, s[8:9]
	global_store_short v[106:107], v108, off sc1
	v_mul_f32_e32 v106, v195, v168
	v_cvt_pk_bf16_f32 v108, v106, s0
	v_lshl_add_u64 v[106:107], v[116:117], 1, s[8:9]
	global_store_short v[106:107], v108, off sc1
	v_mul_f32_e32 v106, v195, v169
	v_cvt_pk_bf16_f32 v108, v106, s0
	v_lshl_add_u64 v[106:107], v[118:119], 1, s[8:9]
	global_store_short v[106:107], v108, off sc1
	v_mul_f32_e32 v106, v195, v167
	v_cvt_pk_bf16_f32 v108, v106, s0
	v_lshl_add_u64 v[106:107], v[120:121], 1, s[8:9]
	global_store_short v[106:107], v108, off sc1
	v_mul_f32_e32 v106, v195, v166
	v_cvt_pk_bf16_f32 v108, v106, s0
	v_lshl_add_u64 v[106:107], v[124:125], 1, s[8:9]
	global_store_short v[106:107], v108, off sc1
	v_mul_f32_e32 v106, v195, v165
	v_cvt_pk_bf16_f32 v108, v106, s0
	v_lshl_add_u64 v[106:107], v[126:127], 1, s[8:9]
	global_store_short v[106:107], v108, off sc1
	v_mul_f32_e32 v106, v195, v103
	v_cvt_pk_bf16_f32 v108, v106, s0
	v_lshl_add_u64 v[106:107], v[128:129], 1, s[8:9]
	global_store_short v[106:107], v108, off sc1
	v_add_f32_e32 v106, 1.0, v132
	v_mul_f32_e32 v110, v133, v106
	v_add_u32_e32 v106, v188, v48
	s_waitcnt vmcnt(24)
	v_fmac_f32_e32 v62, v34, v194
	s_waitcnt vmcnt(17)
	v_fmac_f32_e32 v61, v35, v194
	v_fmac_f32_e32 v60, v36, v194
	v_fmac_f32_e32 v59, v37, v194
	v_fmac_f32_e32 v58, v38, v194
	v_fmac_f32_e32 v57, v39, v194
	v_fmac_f32_e32 v56, v40, v194
	v_fmac_f32_e32 v55, v41, v194
	s_waitcnt vmcnt(16)
	v_fmac_f32_e32 v54, v42, v194
	s_waitcnt vmcnt(15)
	v_fmac_f32_e32 v53, v43, v194
	s_waitcnt vmcnt(14)
	v_fmac_f32_e32 v52, v44, v194
	s_waitcnt vmcnt(13)
	v_fmac_f32_e32 v51, v45, v194
	s_waitcnt vmcnt(12)
	v_fmac_f32_e32 v50, v46, v194
	s_waitcnt vmcnt(11)
	v_fmac_f32_e32 v49, v47, v194
	v_ashrrev_i32_e32 v107, 31, v106
	global_store_dword v[104:105], v196, off offset:128 sc1
	v_mul_f32_e32 v32, v110, v196
	global_store_dword v[84:85], v62, off offset:128 sc1
	global_store_dword v[82:83], v61, off offset:128 sc1
	global_store_dword v[78:79], v60, off offset:128 sc1
	global_store_dword v[72:73], v59, off offset:128 sc1
	global_store_dword v[74:75], v58, off offset:128 sc1
	global_store_dword v[76:77], v57, off offset:128 sc1
	global_store_dword v[80:81], v56, off offset:128 sc1
	global_store_dword v[86:87], v55, off offset:128 sc1
	global_store_dword v[90:91], v54, off offset:128 sc1
	global_store_dword v[92:93], v53, off offset:128 sc1
	global_store_dword v[94:95], v52, off offset:128 sc1
	global_store_dword v[96:97], v51, off offset:128 sc1
	global_store_dword v[98:99], v50, off offset:128 sc1
	global_store_dword v[100:101], v49, off offset:128 sc1
	v_cvt_pk_bf16_f32 v32, v32, s0
	v_lshl_add_u64 v[106:107], v[106:107], 1, s[8:9]
	v_add_u32_e32 v108, v186, v48
	global_load_dword v45, v[88:89], off offset:256
	v_ashrrev_i32_e32 v109, 31, v108
	global_store_short v[106:107], v32, off sc1
	v_mul_f32_e32 v113, v110, v56
	v_cvt_pk_bf16_f32 v113, v113, s0
	v_mul_f32_e32 v106, v196, v196
	s_waitcnt vmcnt(26)
	v_fmac_f32_e32 v63, v33, v194
	v_mul_f32_e32 v32, v110, v63
	v_cvt_pk_bf16_f32 v34, v32, s0
	v_lshl_add_u64 v[32:33], v[108:109], 1, s[8:9]
	global_store_short v[32:33], v34, off sc1
	v_add_u32_e32 v32, v184, v48
	v_ashrrev_i32_e32 v33, 31, v32
	v_mul_f32_e32 v34, v110, v62
	v_cvt_pk_bf16_f32 v34, v34, s0
	v_lshl_add_u64 v[32:33], v[32:33], 1, s[8:9]
	global_store_short v[32:33], v34, off sc1
	v_add_u32_e32 v32, v183, v48
	v_ashrrev_i32_e32 v33, 31, v32
	v_mul_f32_e32 v34, v110, v61
	v_cvt_pk_bf16_f32 v34, v34, s0
	v_lshl_add_u64 v[32:33], v[32:33], 1, s[8:9]
	global_store_short v[32:33], v34, off sc1
	v_add_u32_e32 v32, v181, v48
	v_ashrrev_i32_e32 v33, 31, v32
	v_mul_f32_e32 v34, v110, v60
	v_cvt_pk_bf16_f32 v34, v34, s0
	v_lshl_add_u64 v[32:33], v[32:33], 1, s[8:9]
	global_store_short v[32:33], v34, off sc1
	v_add_u32_e32 v32, v179, v48
	v_ashrrev_i32_e32 v33, 31, v32
	v_mul_f32_e32 v34, v110, v59
	v_cvt_pk_bf16_f32 v42, v34, s0
	v_lshl_add_u64 v[34:35], v[32:33], 1, s[8:9]
	v_or_b32_e32 v32, 64, v102
	v_ashrrev_i32_e32 v33, 31, v32
	v_lshlrev_b64 v[36:37], 2, v[32:33]
	global_store_dword v[88:89], v63, off offset:128 sc1
	v_lshl_add_u64 v[40:41], s[64:65], 0, v[36:37]
	v_lshl_add_u64 v[38:39], s[60:61], 0, v[36:37]
	global_load_dword v107, v[40:41], off
	global_load_dword v111, v[38:39], off
	v_mul_f32_e32 v33, v110, v58
	global_store_short v[34:35], v42, off sc1
	v_lshl_add_u64 v[34:35], s[62:63], 0, v[36:37]
	global_load_dword v112, v[34:35], off
	v_add_u32_e32 v34, v71, v48
	v_ashrrev_i32_e32 v35, 31, v34
	v_cvt_pk_bf16_f32 v33, v33, s0
	v_lshl_add_u64 v[34:35], v[34:35], 1, s[8:9]
	global_store_short v[34:35], v33, off sc1
	v_add_u32_e32 v34, v180, v48
	v_ashrrev_i32_e32 v35, 31, v34
	v_mul_f32_e32 v33, v110, v57
	v_cvt_pk_bf16_f32 v33, v33, s0
	v_lshl_add_u64 v[34:35], v[34:35], 1, s[8:9]
	global_load_dword v38, v[90:91], off offset:256
	global_load_dword v37, v[92:93], off offset:256
	global_load_dword v36, v[94:95], off offset:256
	global_load_dword v114, v[104:105], off offset:256
	global_load_dword v47, v[84:85], off offset:256
	global_load_dword v39, v[86:87], off offset:256
	global_load_dword v46, v[82:83], off offset:256
	global_load_dword v44, v[78:79], off offset:256
	global_load_dword v43, v[72:73], off offset:256
	global_load_dword v42, v[74:75], off offset:256
	global_load_dword v40, v[80:81], off offset:256
	global_load_dword v41, v[76:77], off offset:256
	v_add_u32_e32 v108, v182, v48
	global_store_short v[34:35], v33, off sc1
	global_load_dword v35, v[96:97], off offset:256
	v_ashrrev_i32_e32 v109, 31, v108
	global_load_dword v34, v[98:99], off offset:256
	global_load_dword v33, v[100:101], off offset:256
	v_lshl_add_u64 v[108:109], v[108:109], 1, s[8:9]
	global_store_short v[108:109], v113, off sc1
	v_add_u32_e32 v108, v185, v48
	v_ashrrev_i32_e32 v109, 31, v108
	v_mul_f32_e32 v113, v110, v55
	v_cvt_pk_bf16_f32 v113, v113, s0
	v_lshl_add_u64 v[108:109], v[108:109], 1, s[8:9]
	global_store_short v[108:109], v113, off sc1
	v_add_u32_e32 v108, v187, v48
	v_ashrrev_i32_e32 v109, 31, v108
	v_mul_f32_e32 v113, v110, v54
	v_cvt_pk_bf16_f32 v113, v113, s0
	v_lshl_add_u64 v[108:109], v[108:109], 1, s[8:9]
	global_store_short v[108:109], v113, off sc1
	v_add_u32_e32 v108, v189, v48
	v_ashrrev_i32_e32 v109, 31, v108
	v_mul_f32_e32 v113, v110, v53
	v_cvt_pk_bf16_f32 v113, v113, s0
	v_lshl_add_u64 v[108:109], v[108:109], 1, s[8:9]
	global_store_short v[108:109], v113, off sc1
	v_add_u32_e32 v108, v190, v48
	v_ashrrev_i32_e32 v109, 31, v108
	v_mul_f32_e32 v113, v110, v52
	v_cvt_pk_bf16_f32 v113, v113, s0
	v_lshl_add_u64 v[108:109], v[108:109], 1, s[8:9]
	global_store_short v[108:109], v113, off sc1
	v_add_u32_e32 v108, v191, v48
	v_ashrrev_i32_e32 v109, 31, v108
	v_mul_f32_e32 v113, v110, v51
	v_cvt_pk_bf16_f32 v113, v113, s0
	v_lshl_add_u64 v[108:109], v[108:109], 1, s[8:9]
	global_store_short v[108:109], v113, off sc1
	v_add_u32_e32 v108, v192, v48
	v_ashrrev_i32_e32 v109, 31, v108
	v_mul_f32_e32 v113, v110, v50
	v_cvt_pk_bf16_f32 v113, v113, s0
	v_lshl_add_u64 v[108:109], v[108:109], 1, s[8:9]
	global_store_short v[108:109], v113, off sc1
	v_add_u32_e32 v108, v193, v48
	v_ashrrev_i32_e32 v109, 31, v108
	v_mul_f32_e32 v48, v110, v49
	v_cvt_pk_bf16_f32 v48, v48, s0
	v_lshl_add_u64 v[108:109], v[108:109], 1, s[8:9]
	global_store_short v[108:109], v48, off sc1
	v_add_u32_e32 v108, v188, v32
	v_ashrrev_i32_e32 v109, 31, v108
	s_waitcnt vmcnt(28)
	v_add_f32_e32 v48, 1.0, v107
	s_waitcnt vmcnt(27)
	v_mul_f32_e32 v48, v111, v48
	v_fmac_f32_e32 v106, v197, v197
	s_waitcnt vmcnt(25)
	v_fmac_f32_e32 v45, v17, v112
	global_store_dword v[88:89], v45, off offset:256 sc1
	s_waitcnt vmcnt(24)
	v_fmac_f32_e32 v38, v26, v112
	s_waitcnt vmcnt(23)
	v_fmac_f32_e32 v37, v27, v112
	s_waitcnt vmcnt(22)
	v_fmac_f32_e32 v36, v28, v112
	s_waitcnt vmcnt(21)
	v_fmac_f32_e32 v114, v16, v112
	v_mul_f32_e32 v16, v48, v114
	s_waitcnt vmcnt(20)
	v_fmac_f32_e32 v47, v18, v112
	v_cvt_pk_bf16_f32 v18, v16, s0
	v_lshl_add_u64 v[16:17], v[108:109], 1, s[8:9]
	global_store_short v[16:17], v18, off sc1
	v_add_u32_e32 v16, v186, v32
	v_ashrrev_i32_e32 v17, 31, v16
	v_mul_f32_e32 v18, v48, v45
	v_cvt_pk_bf16_f32 v18, v18, s0
	v_lshl_add_u64 v[16:17], v[16:17], 1, s[8:9]
	global_store_short v[16:17], v18, off sc1
	v_add_u32_e32 v16, v184, v32
	v_ashrrev_i32_e32 v17, 31, v16
	v_mul_f32_e32 v18, v48, v47
	v_cvt_pk_bf16_f32 v18, v18, s0
	v_lshl_add_u64 v[16:17], v[16:17], 1, s[8:9]
	s_waitcnt vmcnt(20)
	v_fmac_f32_e32 v46, v19, v112
	global_store_short v[16:17], v18, off sc1
	v_add_u32_e32 v16, v183, v32
	v_ashrrev_i32_e32 v17, 31, v16
	v_mul_f32_e32 v18, v48, v46
	s_waitcnt vmcnt(20)
	v_fmac_f32_e32 v44, v20, v112
	v_cvt_pk_bf16_f32 v18, v18, s0
	v_lshl_add_u64 v[16:17], v[16:17], 1, s[8:9]
	global_store_short v[16:17], v18, off sc1
	v_mul_f32_e32 v16, v48, v44
	v_cvt_pk_bf16_f32 v26, v16, s0
	v_or_b32_e32 v16, 0x60, v102
	v_add_u32_e32 v18, v181, v32
	v_ashrrev_i32_e32 v17, 31, v16
	s_waitcnt vmcnt(20)
	v_fmac_f32_e32 v43, v21, v112
	s_waitcnt vmcnt(19)
	v_fmac_f32_e32 v42, v22, v112
	s_waitcnt vmcnt(17)
	v_fmac_f32_e32 v41, v23, v112
	v_fmac_f32_e32 v40, v24, v112
	v_fmac_f32_e32 v39, v25, v112
	s_waitcnt vmcnt(15)
	v_fmac_f32_e32 v35, v29, v112
	s_waitcnt vmcnt(14)
	v_fmac_f32_e32 v34, v30, v112
	s_waitcnt vmcnt(13)
	v_fmac_f32_e32 v33, v31, v112
	v_ashrrev_i32_e32 v19, 31, v18
	v_lshlrev_b64 v[20:21], 2, v[16:17]
	global_store_dword v[84:85], v47, off offset:256 sc1
	global_store_dword v[82:83], v46, off offset:256 sc1
	global_store_dword v[78:79], v44, off offset:256 sc1
	global_store_dword v[72:73], v43, off offset:256 sc1
	global_store_dword v[74:75], v42, off offset:256 sc1
	global_store_dword v[76:77], v41, off offset:256 sc1
	global_store_dword v[80:81], v40, off offset:256 sc1
	global_store_dword v[86:87], v39, off offset:256 sc1
	global_store_dword v[90:91], v38, off offset:256 sc1
	global_store_dword v[92:93], v37, off offset:256 sc1
	global_store_dword v[94:95], v36, off offset:256 sc1
	global_store_dword v[96:97], v35, off offset:256 sc1
	global_store_dword v[98:99], v34, off offset:256 sc1
	global_store_dword v[100:101], v33, off offset:256 sc1
	global_store_dword v[104:105], v114, off offset:256 sc1
	v_lshl_add_u64 v[24:25], s[64:65], 0, v[20:21]
	v_lshl_add_u64 v[18:19], v[18:19], 1, s[8:9]
	global_load_dword v29, v[104:105], off offset:384
	v_lshl_add_u64 v[22:23], s[60:61], 0, v[20:21]
	global_load_dword v17, v[24:25], off
	global_load_dword v30, v[22:23], off
	global_load_dword v28, v[88:89], off offset:384
	global_load_dword v27, v[84:85], off offset:384
	v_fmac_f32_e32 v106, v114, v114
	global_store_short v[18:19], v26, off sc1
	v_lshl_add_u64 v[18:19], s[62:63], 0, v[20:21]
	global_load_dword v102, v[18:19], off
	v_add_u32_e32 v18, v179, v32
	v_ashrrev_i32_e32 v19, 31, v18
	v_mul_f32_e32 v20, v48, v43
	v_cvt_pk_bf16_f32 v20, v20, s0
	v_lshl_add_u64 v[18:19], v[18:19], 1, s[8:9]
	global_store_short v[18:19], v20, off sc1
	v_add_u32_e32 v18, v71, v32
	v_ashrrev_i32_e32 v19, 31, v18
	v_mul_f32_e32 v20, v48, v42
	v_cvt_pk_bf16_f32 v20, v20, s0
	v_lshl_add_u64 v[18:19], v[18:19], 1, s[8:9]
	global_store_short v[18:19], v20, off sc1
	v_add_u32_e32 v18, v180, v32
	v_ashrrev_i32_e32 v19, 31, v18
	v_mul_f32_e32 v20, v48, v41
	v_cvt_pk_bf16_f32 v20, v20, s0
	v_lshl_add_u64 v[18:19], v[18:19], 1, s[8:9]
	global_store_short v[18:19], v20, off sc1
	v_add_u32_e32 v18, v182, v32
	v_ashrrev_i32_e32 v19, 31, v18
	v_mul_f32_e32 v20, v48, v40
	v_cvt_pk_bf16_f32 v20, v20, s0
	v_lshl_add_u64 v[18:19], v[18:19], 1, s[8:9]
	global_store_short v[18:19], v20, off sc1
	v_add_u32_e32 v18, v185, v32
	v_ashrrev_i32_e32 v19, 31, v18
	v_mul_f32_e32 v20, v48, v39
	v_cvt_pk_bf16_f32 v20, v20, s0
	v_lshl_add_u64 v[18:19], v[18:19], 1, s[8:9]
	global_store_short v[18:19], v20, off sc1
	v_add_u32_e32 v18, v187, v32
	v_ashrrev_i32_e32 v19, 31, v18
	v_mul_f32_e32 v20, v48, v38
	v_cvt_pk_bf16_f32 v20, v20, s0
	v_lshl_add_u64 v[18:19], v[18:19], 1, s[8:9]
	global_store_short v[18:19], v20, off sc1
	v_add_u32_e32 v18, v189, v32
	v_ashrrev_i32_e32 v19, 31, v18
	v_mul_f32_e32 v20, v48, v37
	v_cvt_pk_bf16_f32 v20, v20, s0
	v_lshl_add_u64 v[18:19], v[18:19], 1, s[8:9]
	global_store_short v[18:19], v20, off sc1
	v_add_u32_e32 v18, v190, v32
	v_ashrrev_i32_e32 v19, 31, v18
	v_mul_f32_e32 v20, v48, v36
	v_cvt_pk_bf16_f32 v20, v20, s0
	v_lshl_add_u64 v[18:19], v[18:19], 1, s[8:9]
	global_store_short v[18:19], v20, off sc1
	v_add_u32_e32 v18, v191, v32
	v_ashrrev_i32_e32 v19, 31, v18
	v_mul_f32_e32 v20, v48, v35
	v_cvt_pk_bf16_f32 v20, v20, s0
	v_lshl_add_u64 v[18:19], v[18:19], 1, s[8:9]
	global_store_short v[18:19], v20, off sc1
	v_add_u32_e32 v18, v192, v32
	v_ashrrev_i32_e32 v19, 31, v18
	v_mul_f32_e32 v20, v48, v34
	v_cvt_pk_bf16_f32 v20, v20, s0
	v_lshl_add_u64 v[18:19], v[18:19], 1, s[8:9]
	global_store_short v[18:19], v20, off sc1
	v_add_u32_e32 v18, v193, v32
	v_ashrrev_i32_e32 v19, 31, v18
	v_mul_f32_e32 v20, v48, v33
	v_cvt_pk_bf16_f32 v20, v20, s0
	v_lshl_add_u64 v[18:19], v[18:19], 1, s[8:9]
	global_store_short v[18:19], v20, off sc1
	global_load_dword v20, v[86:87], off offset:384
	v_add_u32_e32 v18, v188, v16
	global_load_dword v26, v[82:83], off offset:384
	global_load_dword v25, v[78:79], off offset:384
	global_load_dword v24, v[72:73], off offset:384
	global_load_dword v23, v[74:75], off offset:384
	global_load_dword v21, v[80:81], off offset:384
	global_load_dword v22, v[76:77], off offset:384
	s_waitcnt vmcnt(23)
	v_add_f32_e32 v17, 1.0, v17
	s_waitcnt vmcnt(22)
	v_mul_f32_e32 v32, v30, v17
	v_ashrrev_i32_e32 v19, 31, v18
	v_lshl_add_u64 v[18:19], v[18:19], 1, s[8:9]
	v_add_u32_e32 v30, v186, v16
	s_waitcnt vmcnt(18)
	v_fmac_f32_e32 v29, v0, v102
	v_mul_f32_e32 v0, v32, v29
	v_cvt_pk_bf16_f32 v0, v0, s0
	global_store_short v[18:19], v0, off sc1
	global_load_dword v19, v[90:91], off offset:384
	v_ashrrev_i32_e32 v31, 31, v30
	global_load_dword v18, v[92:93], off offset:384
	v_fmac_f32_e32 v28, v1, v102
	v_mul_f32_e32 v0, v32, v28
	v_cvt_pk_bf16_f32 v17, v0, s0
	v_lshl_add_u64 v[0:1], v[30:31], 1, s[8:9]
	global_store_short v[0:1], v17, off sc1
	v_add_u32_e32 v0, v184, v16
	v_fmac_f32_e32 v27, v2, v102
	global_load_dword v17, v[94:95], off offset:384
	v_ashrrev_i32_e32 v1, 31, v0
	v_mul_f32_e32 v2, v32, v27
	v_cvt_pk_bf16_f32 v2, v2, s0
	v_lshl_add_u64 v[0:1], v[0:1], 1, s[8:9]
	global_store_short v[0:1], v2, off sc1
	v_add_u32_e32 v0, v183, v16
	global_load_dword v2, v[96:97], off offset:384
	v_ashrrev_i32_e32 v1, 31, v0
	v_lshl_add_u64 v[0:1], v[0:1], 1, s[8:9]
	v_add_u32_e32 v30, v181, v16
	v_ashrrev_i32_e32 v31, 31, v30
	v_lshl_add_u64 v[30:31], v[30:31], 1, s[8:9]
	v_fmac_f32_e32 v106, v29, v29
	global_store_dword v[104:105], v29, off offset:384 sc1
	global_store_dword v[88:89], v28, off offset:384 sc1
	global_store_dword v[84:85], v27, off offset:384 sc1
	s_waitcnt vmcnt(16)
	v_fmac_f32_e32 v20, v9, v102
	global_store_dword v[86:87], v20, off offset:384 sc1
	s_waitcnt vmcnt(16)
	v_fmac_f32_e32 v26, v3, v102
	v_mul_f32_e32 v3, v32, v26
	v_cvt_pk_bf16_f32 v3, v3, s0
	global_store_short v[0:1], v3, off sc1
	global_load_dword v1, v[98:99], off offset:384
	s_waitcnt vmcnt(17)
	v_fmac_f32_e32 v25, v4, v102
	v_mul_f32_e32 v0, v32, v25
	v_cvt_pk_bf16_f32 v0, v0, s0
	global_store_short v[30:31], v0, off sc1
	global_load_dword v0, v[100:101], off offset:384
	v_add_u32_e32 v30, v179, v16
	s_waitcnt vmcnt(18)
	v_fmac_f32_e32 v24, v5, v102
	v_ashrrev_i32_e32 v31, 31, v30
	v_mul_f32_e32 v3, v32, v24
	v_cvt_pk_bf16_f32 v3, v3, s0
	v_lshl_add_u64 v[4:5], v[30:31], 1, s[8:9]
	global_store_short v[4:5], v3, off sc1
	v_add_u32_e32 v4, v71, v16
	s_waitcnt vmcnt(18)
	v_fmac_f32_e32 v23, v6, v102
	v_ashrrev_i32_e32 v5, 31, v4
	v_mul_f32_e32 v3, v32, v23
	v_cvt_pk_bf16_f32 v3, v3, s0
	v_lshl_add_u64 v[4:5], v[4:5], 1, s[8:9]
	global_store_short v[4:5], v3, off sc1
	v_add_u32_e32 v4, v180, v16
	s_waitcnt vmcnt(17)
	v_fmac_f32_e32 v22, v7, v102
	v_ashrrev_i32_e32 v5, 31, v4
	v_mul_f32_e32 v3, v32, v22
	v_cvt_pk_bf16_f32 v3, v3, s0
	v_lshl_add_u64 v[4:5], v[4:5], 1, s[8:9]
	global_store_short v[4:5], v3, off sc1
	v_add_u32_e32 v4, v182, v16
	v_fmac_f32_e32 v21, v8, v102
	v_ashrrev_i32_e32 v5, 31, v4
	v_mul_f32_e32 v3, v32, v21
	v_cvt_pk_bf16_f32 v3, v3, s0
	v_lshl_add_u64 v[4:5], v[4:5], 1, s[8:9]
	global_store_short v[4:5], v3, off sc1
	v_add_u32_e32 v4, v185, v16
	v_ashrrev_i32_e32 v5, 31, v4
	v_mul_f32_e32 v3, v32, v20
	v_cvt_pk_bf16_f32 v3, v3, s0
	v_lshl_add_u64 v[4:5], v[4:5], 1, s[8:9]
	global_store_short v[4:5], v3, off sc1
	v_add_u32_e32 v4, v187, v16
	s_waitcnt vmcnt(18)
	v_fmac_f32_e32 v19, v10, v102
	v_ashrrev_i32_e32 v5, 31, v4
	v_mul_f32_e32 v3, v32, v19
	v_cvt_pk_bf16_f32 v3, v3, s0
	v_lshl_add_u64 v[4:5], v[4:5], 1, s[8:9]
	global_store_short v[4:5], v3, off sc1
	v_add_u32_e32 v4, v189, v16
	s_waitcnt vmcnt(18)
	v_fmac_f32_e32 v18, v11, v102
	v_ashrrev_i32_e32 v5, 31, v4
	v_mul_f32_e32 v3, v32, v18
	v_cvt_pk_bf16_f32 v3, v3, s0
	v_lshl_add_u64 v[4:5], v[4:5], 1, s[8:9]
	global_store_short v[4:5], v3, off sc1
	v_add_u32_e32 v4, v190, v16
	s_waitcnt vmcnt(17)
	v_fmac_f32_e32 v17, v12, v102
	v_ashrrev_i32_e32 v5, 31, v4
	v_mul_f32_e32 v3, v32, v17
	v_cvt_pk_bf16_f32 v3, v3, s0
	v_lshl_add_u64 v[4:5], v[4:5], 1, s[8:9]
	global_store_short v[4:5], v3, off sc1
	v_add_u32_e32 v4, v191, v16
	s_waitcnt vmcnt(16)
	v_fmac_f32_e32 v2, v13, v102
	v_ashrrev_i32_e32 v5, 31, v4
	v_mul_f32_e32 v3, v32, v2
	v_cvt_pk_bf16_f32 v3, v3, s0
	v_lshl_add_u64 v[4:5], v[4:5], 1, s[8:9]
	global_store_short v[4:5], v3, off sc1
	v_add_u32_e32 v4, v192, v16
	v_ashrrev_i32_e32 v5, 31, v4
	v_lshl_add_u64 v[4:5], v[4:5], 1, s[8:9]
	v_xor_b32_e32 v13, 16, v164
	v_add_u32_e32 v10, v193, v16
	v_ashrrev_i32_e32 v11, 31, v10
	v_lshl_add_u64 v[10:11], v[10:11], 1, s[8:9]
	v_ashrrev_i32_e32 v71, 31, v70
	global_store_dword v[82:83], v26, off offset:384 sc1
	global_store_dword v[78:79], v25, off offset:384 sc1
	global_store_dword v[72:73], v24, off offset:384 sc1
	global_store_dword v[74:75], v23, off offset:384 sc1
	s_waitcnt vmcnt(15)
	v_fmac_f32_e32 v1, v14, v102
	v_mul_f32_e32 v3, v32, v1
	v_cvt_pk_bf16_f32 v3, v3, s0
	global_store_short v[4:5], v3, off sc1
	v_and_b32_e32 v4, 64, v164
	v_xor_b32_e32 v3, 1, v164
	v_add_u32_e32 v7, 64, v4
	v_cmp_lt_i32_e32 vcc, v3, v7
	v_xor_b32_e32 v4, 2, v164
	s_waitcnt vmcnt(14)
	v_fmac_f32_e32 v0, v15, v102
	v_cndmask_b32_e32 v3, v164, v3, vcc
	v_lshlrev_b32_e32 v3, 2, v3
	ds_bpermute_b32 v5, v3, v106
	v_cmp_lt_i32_e32 vcc, v4, v7
	v_mul_f32_e32 v12, v32, v0
	v_cvt_pk_bf16_f32 v12, v12, s0
	v_cndmask_b32_e32 v4, v164, v4, vcc
	v_lshlrev_b32_e32 v4, 2, v4
	s_waitcnt lgkmcnt(0)
	v_add_f32_e32 v6, v106, v5
	ds_bpermute_b32 v8, v4, v6
	v_xor_b32_e32 v5, 4, v164
	v_cmp_lt_i32_e32 vcc, v5, v7
	global_store_dword v[76:77], v22, off offset:384 sc1
	global_store_dword v[80:81], v21, off offset:384 sc1
	v_cndmask_b32_e32 v5, v164, v5, vcc
	v_lshlrev_b32_e32 v5, 2, v5
	s_waitcnt lgkmcnt(0)
	v_add_f32_e32 v8, v6, v8
	ds_bpermute_b32 v9, v5, v8
	v_xor_b32_e32 v6, 8, v164
	v_cmp_lt_i32_e32 vcc, v6, v7
	global_store_dword v[90:91], v19, off offset:384 sc1
	global_store_dword v[92:93], v18, off offset:384 sc1
	v_cndmask_b32_e32 v6, v164, v6, vcc
	v_lshlrev_b32_e32 v6, 2, v6
	s_waitcnt lgkmcnt(0)
	v_add_f32_e32 v8, v8, v9
	ds_bpermute_b32 v9, v6, v8
	v_cmp_lt_i32_e32 vcc, v13, v7
	global_store_dword v[94:95], v17, off offset:384 sc1
	global_store_dword v[96:97], v2, off offset:384 sc1
	v_cndmask_b32_e32 v7, v164, v13, vcc
	v_lshlrev_b32_e32 v7, 2, v7
	s_waitcnt lgkmcnt(0)
	v_add_f32_e32 v8, v8, v9
	ds_bpermute_b32 v9, v7, v8
	global_store_dword v[98:99], v1, off offset:384 sc1
	global_store_dword v[100:101], v0, off offset:384 sc1
	global_store_short v[10:11], v12, off sc1
	s_and_saveexec_b64 s[60:61], s[0:1]
	s_cbranch_execz .LBB0_1052
	s_waitcnt lgkmcnt(0)
	v_add_f32_e32 v10, v8, v9
	v_lshl_add_u64 v[8:9], v[70:71], 2, s[58:59]
	global_store_dword v[8:9], v10, off sc1
.LBB0_1052:
	s_or_b64 exec, exec, s[60:61]
	v_mul_f32_e32 v8, v63, v63
	v_fmac_f32_e32 v8, v178, v178
	v_fmac_f32_e32 v8, v45, v45
	v_fmac_f32_e32 v8, v28, v28
	s_waitcnt lgkmcnt(0)
	ds_bpermute_b32 v9, v3, v8
	s_waitcnt lgkmcnt(0)
	v_add_f32_e32 v8, v8, v9
	ds_bpermute_b32 v9, v4, v8
	s_waitcnt lgkmcnt(0)
	v_add_f32_e32 v8, v8, v9
	ds_bpermute_b32 v9, v5, v8
	s_waitcnt lgkmcnt(0)
	v_add_f32_e32 v8, v8, v9
	ds_bpermute_b32 v9, v6, v8
	s_waitcnt lgkmcnt(0)
	v_add_f32_e32 v8, v8, v9
	ds_bpermute_b32 v9, v7, v8
	s_and_saveexec_b64 s[60:61], s[0:1]
	s_cbranch_execz .LBB0_1054
	s_waitcnt lgkmcnt(0)
	v_add_f32_e32 v10, v8, v9
	v_lshl_add_u64 v[8:9], v[70:71], 2, s[58:59]
	global_store_dword v[8:9], v10, off offset:4 sc1
.LBB0_1054:
	s_or_b64 exec, exec, s[60:61]
	v_mul_f32_e32 v8, v62, v62
	v_fmac_f32_e32 v8, v177, v177
	v_fmac_f32_e32 v8, v47, v47
	v_fmac_f32_e32 v8, v27, v27
	s_waitcnt lgkmcnt(0)
	ds_bpermute_b32 v9, v3, v8
	s_waitcnt lgkmcnt(0)
	v_add_f32_e32 v8, v8, v9
	ds_bpermute_b32 v9, v4, v8
	s_waitcnt lgkmcnt(0)
	v_add_f32_e32 v8, v8, v9
	ds_bpermute_b32 v9, v5, v8
	s_waitcnt lgkmcnt(0)
	v_add_f32_e32 v8, v8, v9
	ds_bpermute_b32 v9, v6, v8
	s_waitcnt lgkmcnt(0)
	v_add_f32_e32 v8, v8, v9
	ds_bpermute_b32 v9, v7, v8
	s_and_saveexec_b64 s[60:61], s[0:1]
	s_cbranch_execz .LBB0_1056
	s_waitcnt lgkmcnt(0)
	v_add_f32_e32 v10, v8, v9
	v_lshl_add_u64 v[8:9], v[70:71], 2, s[58:59]
	global_store_dword v[8:9], v10, off offset:8 sc1
.LBB0_1056:
	s_or_b64 exec, exec, s[60:61]
	v_mul_f32_e32 v8, v61, v61
	v_fmac_f32_e32 v8, v176, v176
	v_fmac_f32_e32 v8, v46, v46
	v_fmac_f32_e32 v8, v26, v26
	s_waitcnt lgkmcnt(0)
	ds_bpermute_b32 v9, v3, v8
	s_waitcnt lgkmcnt(0)
	v_add_f32_e32 v8, v8, v9
	ds_bpermute_b32 v9, v4, v8
	s_waitcnt lgkmcnt(0)
	v_add_f32_e32 v8, v8, v9
	ds_bpermute_b32 v9, v5, v8
	s_waitcnt lgkmcnt(0)
	v_add_f32_e32 v8, v8, v9
	ds_bpermute_b32 v9, v6, v8
	s_waitcnt lgkmcnt(0)
	v_add_f32_e32 v8, v8, v9
	ds_bpermute_b32 v9, v7, v8
	s_and_saveexec_b64 s[60:61], s[0:1]
	s_cbranch_execz .LBB0_1058
	s_waitcnt lgkmcnt(0)
	v_add_f32_e32 v10, v8, v9
	v_lshl_add_u64 v[8:9], v[70:71], 2, s[58:59]
	global_store_dword v[8:9], v10, off offset:12 sc1
.LBB0_1058:
	s_or_b64 exec, exec, s[60:61]
	v_mul_f32_e32 v8, v60, v60
	v_fmac_f32_e32 v8, v175, v175
	v_fmac_f32_e32 v8, v44, v44
	v_fmac_f32_e32 v8, v25, v25
	s_waitcnt lgkmcnt(0)
	ds_bpermute_b32 v9, v3, v8
	s_waitcnt lgkmcnt(0)
	v_add_f32_e32 v8, v8, v9
	ds_bpermute_b32 v9, v4, v8
	s_waitcnt lgkmcnt(0)
	v_add_f32_e32 v8, v8, v9
	ds_bpermute_b32 v9, v5, v8
	s_waitcnt lgkmcnt(0)
	v_add_f32_e32 v8, v8, v9
	ds_bpermute_b32 v9, v6, v8
	s_waitcnt lgkmcnt(0)
	v_add_f32_e32 v8, v8, v9
	ds_bpermute_b32 v9, v7, v8
	s_and_saveexec_b64 s[60:61], s[0:1]
	s_cbranch_execz .LBB0_1060
	s_waitcnt lgkmcnt(0)
	v_add_f32_e32 v10, v8, v9
	v_lshl_add_u64 v[8:9], v[70:71], 2, s[58:59]
	global_store_dword v[8:9], v10, off offset:32 sc1
.LBB0_1060:
	s_or_b64 exec, exec, s[60:61]
	v_mul_f32_e32 v8, v59, v59
	v_fmac_f32_e32 v8, v174, v174
	v_fmac_f32_e32 v8, v43, v43
	v_fmac_f32_e32 v8, v24, v24
	s_waitcnt lgkmcnt(0)
	ds_bpermute_b32 v9, v3, v8
	s_waitcnt lgkmcnt(0)
	v_add_f32_e32 v8, v8, v9
	ds_bpermute_b32 v9, v4, v8
	s_waitcnt lgkmcnt(0)
	v_add_f32_e32 v8, v8, v9
	ds_bpermute_b32 v9, v5, v8
	s_waitcnt lgkmcnt(0)
	v_add_f32_e32 v8, v8, v9
	ds_bpermute_b32 v9, v6, v8
	s_waitcnt lgkmcnt(0)
	v_add_f32_e32 v8, v8, v9
	ds_bpermute_b32 v9, v7, v8
	s_and_saveexec_b64 s[60:61], s[0:1]
	s_cbranch_execz .LBB0_1062
	s_waitcnt lgkmcnt(0)
	v_add_f32_e32 v10, v8, v9
	v_lshl_add_u64 v[8:9], v[70:71], 2, s[58:59]
	global_store_dword v[8:9], v10, off offset:36 sc1
.LBB0_1062:
	s_or_b64 exec, exec, s[60:61]
	v_mul_f32_e32 v8, v58, v58
	v_fmac_f32_e32 v8, v173, v173
	v_fmac_f32_e32 v8, v42, v42
	v_fmac_f32_e32 v8, v23, v23
	s_waitcnt lgkmcnt(0)
	ds_bpermute_b32 v9, v3, v8
	s_waitcnt lgkmcnt(0)
	v_add_f32_e32 v8, v8, v9
	ds_bpermute_b32 v9, v4, v8
	s_waitcnt lgkmcnt(0)
	v_add_f32_e32 v8, v8, v9
	ds_bpermute_b32 v9, v5, v8
	s_waitcnt lgkmcnt(0)
	v_add_f32_e32 v8, v8, v9
	ds_bpermute_b32 v9, v6, v8
	s_waitcnt lgkmcnt(0)
	v_add_f32_e32 v8, v8, v9
	ds_bpermute_b32 v9, v7, v8
	s_and_saveexec_b64 s[60:61], s[0:1]
	s_cbranch_execz .LBB0_1064
	s_waitcnt lgkmcnt(0)
	v_add_f32_e32 v10, v8, v9
	v_lshl_add_u64 v[8:9], v[70:71], 2, s[58:59]
	global_store_dword v[8:9], v10, off offset:40 sc1
.LBB0_1064:
	s_or_b64 exec, exec, s[60:61]
	v_mul_f32_e32 v8, v57, v57
	v_fmac_f32_e32 v8, v172, v172
	v_fmac_f32_e32 v8, v41, v41
	v_fmac_f32_e32 v8, v22, v22
	s_waitcnt lgkmcnt(0)
	ds_bpermute_b32 v9, v3, v8
	s_waitcnt lgkmcnt(0)
	v_add_f32_e32 v8, v8, v9
	ds_bpermute_b32 v9, v4, v8
	s_waitcnt lgkmcnt(0)
	v_add_f32_e32 v8, v8, v9
	ds_bpermute_b32 v9, v5, v8
	s_waitcnt lgkmcnt(0)
	v_add_f32_e32 v8, v8, v9
	ds_bpermute_b32 v9, v6, v8
	s_waitcnt lgkmcnt(0)
	v_add_f32_e32 v8, v8, v9
	ds_bpermute_b32 v9, v7, v8
	s_and_saveexec_b64 s[60:61], s[0:1]
	s_cbranch_execz .LBB0_1066
	s_waitcnt lgkmcnt(0)
	v_add_f32_e32 v10, v8, v9
	v_lshl_add_u64 v[8:9], v[70:71], 2, s[58:59]
	global_store_dword v[8:9], v10, off offset:44 sc1
.LBB0_1066:
	s_or_b64 exec, exec, s[60:61]
	v_mul_f32_e32 v8, v56, v56
	v_fmac_f32_e32 v8, v171, v171
	v_fmac_f32_e32 v8, v40, v40
	v_fmac_f32_e32 v8, v21, v21
	s_waitcnt lgkmcnt(0)
	ds_bpermute_b32 v9, v3, v8
	s_waitcnt lgkmcnt(0)
	v_add_f32_e32 v8, v8, v9
	ds_bpermute_b32 v9, v4, v8
	s_waitcnt lgkmcnt(0)
	v_add_f32_e32 v8, v8, v9
	ds_bpermute_b32 v9, v5, v8
	s_waitcnt lgkmcnt(0)
	v_add_f32_e32 v8, v8, v9
	ds_bpermute_b32 v9, v6, v8
	s_waitcnt lgkmcnt(0)
	v_add_f32_e32 v8, v8, v9
	ds_bpermute_b32 v9, v7, v8
	s_and_saveexec_b64 s[60:61], s[0:1]
	s_cbranch_execz .LBB0_1068
	s_waitcnt lgkmcnt(0)
	v_add_f32_e32 v10, v8, v9
	v_lshl_add_u64 v[8:9], v[70:71], 2, s[58:59]
	global_store_dword v[8:9], v10, off offset:64 sc1
.LBB0_1068:
	s_or_b64 exec, exec, s[60:61]
	v_mul_f32_e32 v8, v55, v55
	v_fmac_f32_e32 v8, v170, v170
	v_fmac_f32_e32 v8, v39, v39
	v_fmac_f32_e32 v8, v20, v20
	s_waitcnt lgkmcnt(0)
	ds_bpermute_b32 v9, v3, v8
	s_waitcnt lgkmcnt(0)
	v_add_f32_e32 v8, v8, v9
	ds_bpermute_b32 v9, v4, v8
	s_waitcnt lgkmcnt(0)
	v_add_f32_e32 v8, v8, v9
	ds_bpermute_b32 v9, v5, v8
	s_waitcnt lgkmcnt(0)
	v_add_f32_e32 v8, v8, v9
	ds_bpermute_b32 v9, v6, v8
	s_waitcnt lgkmcnt(0)
	v_add_f32_e32 v8, v8, v9
	ds_bpermute_b32 v9, v7, v8
	s_and_saveexec_b64 s[60:61], s[0:1]
	s_cbranch_execz .LBB0_1070
	s_waitcnt lgkmcnt(0)
	v_add_f32_e32 v10, v8, v9
	v_lshl_add_u64 v[8:9], v[70:71], 2, s[58:59]
	global_store_dword v[8:9], v10, off offset:68 sc1
.LBB0_1070:
	s_or_b64 exec, exec, s[60:61]
	v_mul_f32_e32 v8, v54, v54
	v_fmac_f32_e32 v8, v168, v168
	v_fmac_f32_e32 v8, v38, v38
	v_fmac_f32_e32 v8, v19, v19
	s_waitcnt lgkmcnt(0)
	ds_bpermute_b32 v9, v3, v8
	s_waitcnt lgkmcnt(0)
	v_add_f32_e32 v8, v8, v9
	ds_bpermute_b32 v9, v4, v8
	s_waitcnt lgkmcnt(0)
	v_add_f32_e32 v8, v8, v9
	ds_bpermute_b32 v9, v5, v8
	s_waitcnt lgkmcnt(0)
	v_add_f32_e32 v8, v8, v9
	ds_bpermute_b32 v9, v6, v8
	s_waitcnt lgkmcnt(0)
	v_add_f32_e32 v8, v8, v9
	ds_bpermute_b32 v9, v7, v8
	s_and_saveexec_b64 s[60:61], s[0:1]
	s_cbranch_execz .LBB0_1072
	s_waitcnt lgkmcnt(0)
	v_add_f32_e32 v10, v8, v9
	v_lshl_add_u64 v[8:9], v[70:71], 2, s[58:59]
	global_store_dword v[8:9], v10, off offset:72 sc1
.LBB0_1072:
	s_or_b64 exec, exec, s[60:61]
	v_mul_f32_e32 v8, v53, v53
	v_fmac_f32_e32 v8, v169, v169
	v_fmac_f32_e32 v8, v37, v37
	v_fmac_f32_e32 v8, v18, v18
	s_waitcnt lgkmcnt(0)
	ds_bpermute_b32 v9, v3, v8
	s_waitcnt lgkmcnt(0)
	v_add_f32_e32 v8, v8, v9
	ds_bpermute_b32 v9, v4, v8
	s_waitcnt lgkmcnt(0)
	v_add_f32_e32 v8, v8, v9
	ds_bpermute_b32 v9, v5, v8
	s_waitcnt lgkmcnt(0)
	v_add_f32_e32 v8, v8, v9
	ds_bpermute_b32 v9, v6, v8
	s_waitcnt lgkmcnt(0)
	v_add_f32_e32 v8, v8, v9
	ds_bpermute_b32 v9, v7, v8
	s_and_saveexec_b64 s[60:61], s[0:1]
	s_cbranch_execz .LBB0_1074
	s_waitcnt lgkmcnt(0)
	v_add_f32_e32 v10, v8, v9
	v_lshl_add_u64 v[8:9], v[70:71], 2, s[58:59]
	global_store_dword v[8:9], v10, off offset:76 sc1
.LBB0_1074:
	s_or_b64 exec, exec, s[60:61]
	v_mul_f32_e32 v8, v52, v52
	v_fmac_f32_e32 v8, v167, v167
	v_fmac_f32_e32 v8, v36, v36
	v_fmac_f32_e32 v8, v17, v17
	s_waitcnt lgkmcnt(0)
	ds_bpermute_b32 v9, v3, v8
	s_waitcnt lgkmcnt(0)
	v_add_f32_e32 v8, v8, v9
	ds_bpermute_b32 v9, v4, v8
	s_waitcnt lgkmcnt(0)
	v_add_f32_e32 v8, v8, v9
	ds_bpermute_b32 v9, v5, v8
	s_waitcnt lgkmcnt(0)
	v_add_f32_e32 v8, v8, v9
	ds_bpermute_b32 v9, v6, v8
	s_waitcnt lgkmcnt(0)
	v_add_f32_e32 v8, v8, v9
	ds_bpermute_b32 v9, v7, v8
	s_and_saveexec_b64 s[60:61], s[0:1]
	s_cbranch_execz .LBB0_1076
	s_waitcnt lgkmcnt(0)
	v_add_f32_e32 v10, v8, v9
	v_lshl_add_u64 v[8:9], v[70:71], 2, s[58:59]
	global_store_dword v[8:9], v10, off offset:96 sc1
.LBB0_1076:
	s_or_b64 exec, exec, s[60:61]
	v_mul_f32_e32 v8, v51, v51
	v_fmac_f32_e32 v8, v166, v166
	v_fmac_f32_e32 v8, v35, v35
	v_fmac_f32_e32 v8, v2, v2
	ds_bpermute_b32 v2, v3, v8
	s_waitcnt lgkmcnt(0)
	v_add_f32_e32 v2, v8, v2
	ds_bpermute_b32 v8, v4, v2
	s_waitcnt lgkmcnt(0)
	v_add_f32_e32 v2, v2, v8
	ds_bpermute_b32 v8, v5, v2
	s_waitcnt lgkmcnt(0)
	v_add_f32_e32 v2, v2, v8
	ds_bpermute_b32 v8, v6, v2
	s_waitcnt lgkmcnt(0)
	v_add_f32_e32 v2, v2, v8
	ds_bpermute_b32 v8, v7, v2
	s_and_saveexec_b64 s[60:61], s[0:1]
	s_cbranch_execz .LBB0_1078
	s_waitcnt lgkmcnt(0)
	v_add_f32_e32 v2, v2, v8
	v_lshl_add_u64 v[8:9], v[70:71], 2, s[58:59]
	global_store_dword v[8:9], v2, off offset:100 sc1
.LBB0_1078:
	s_or_b64 exec, exec, s[60:61]
	v_mul_f32_e32 v2, v50, v50
	v_fmac_f32_e32 v2, v165, v165
	v_fmac_f32_e32 v2, v34, v34
	v_fmac_f32_e32 v2, v1, v1
	ds_bpermute_b32 v1, v3, v2
	s_waitcnt lgkmcnt(0)
	v_add_f32_e32 v1, v2, v1
	ds_bpermute_b32 v2, v4, v1
	s_waitcnt lgkmcnt(0)
	v_add_f32_e32 v1, v1, v2
	ds_bpermute_b32 v2, v5, v1
	s_waitcnt lgkmcnt(0)
	v_add_f32_e32 v1, v1, v2
	ds_bpermute_b32 v2, v6, v1
	s_waitcnt lgkmcnt(0)
	v_add_f32_e32 v1, v1, v2
	ds_bpermute_b32 v2, v7, v1
	s_and_saveexec_b64 s[60:61], s[0:1]
	s_cbranch_execz .LBB0_1080
	s_waitcnt lgkmcnt(0)
	v_add_f32_e32 v1, v1, v2
	v_lshl_add_u64 v[8:9], v[70:71], 2, s[58:59]
	global_store_dword v[8:9], v1, off offset:104 sc1

.LBB0_1082:
	s_cmp_gt_i32 s17, 12
	s_cselect_b64 s[6:7], -1, 0
	s_and_b64 s[0:1], s[4:5], s[6:7]
	s_andn2_b64 vcc, exec, s[0:1]
	s_cbranch_vccnz .LBB0_1094
	s_waitcnt vmcnt(0)
	v_or_b32_e32 v0, v201, v200
	s_movk_i32 s0, 0x3ff
	v_and_or_b32 v0, v0, s0, v199
	v_cmp_eq_u32_e32 vcc, 0, v0
	s_waitcnt lgkmcnt(0)
	s_barrier
	s_and_saveexec_b64 s[0:1], vcc
	s_cbranch_execz .LBB0_1093
	s_add_u32 s4, s14, 0x5be8c00
	s_addc_u32 s5, s15, 0
	s_lshl_b32 s3, s2, 1
	v_mov_b32_e32 v0, s3
	v_mov_b32_e32 v1, 0x930c
	global_store_short v0, v1, s[4:5] sc1
	s_cmp_lg_u32 s2, 0
	s_cbranch_scc1 .Lgbar_wait_11
	s_lshr_b32 s3, s33, 3
	s_bfm_b64 s[8:9], s3, 0
	s_cmpk_gt_u32 s33, 0x1ff
	s_cselect_b64 s[8:9], -1, s[8:9]
	s_mov_b64 exec, -1
	v_mbcnt_lo_u32_b32 v229, -1, 0
	v_mbcnt_hi_u32_b32 v229, -1, v229
	v_lshlrev_b32_e32 v229, 4, v229
	s_mov_b32 s10, 0x930c930c
	s_mov_b64 exec, s[8:9]

.LBB0_1094:
	s_cmp_lt_i32 s16, 13
	s_cselect_b64 s[0:1], -1, 0
	s_and_b64 s[4:5], s[0:1], s[6:7]
	s_andn2_b64 vcc, exec, s[4:5]
	s_cbranch_vccnz .LBB0_1102
	s_ashr_i32 s3, s2, 31
	s_and_b32 s3, s3, s33
	s_add_i32 s3, s3, s2
	s_cmpk_gt_i32 s3, 0x15ff
	s_cbranch_scc1 .LBB0_1102
	v_lshrrev_b32_e32 v0, 3, v199
	s_waitcnt lgkmcnt(0)
	v_lshrrev_b32_e32 v1, 5, v199
	v_bfe_u32 v4, v199, 1, 3
	v_lshlrev_b32_e32 v5, 4, v199
	v_bfe_u32 v2, v199, 5, 1
	v_xor_b32_e32 v6, v5, v199
	v_lshlrev_b32_e32 v7, 11, v0
	s_movk_i32 s4, 0x70
	v_bitop3_b32 v1, v1, v4, 1 bitop3:0x6c
	v_and_or_b32 v76, v6, s4, v7
	v_lshlrev_b32_e32 v7, 4, v1
	v_bitop3_b32 v1, v2, v4, 2 bitop3:0x36
	v_lshrrev_b32_e32 v3, 1, v199
	v_lshlrev_b32_e32 v9, 4, v1
	v_bitop3_b32 v1, v2, v4, 4 bitop3:0x36
	v_mov_b32_e32 v77, 0
	v_and_b32_e32 v3, 0x1e0, v3
	v_lshlrev_b32_e32 v10, 4, v1
	v_bitop3_b32 v1, v2, v4, 6 bitop3:0x36
	v_lshlrev_b32_e32 v2, 4, v1
	v_and_or_b32 v93, v0, 4, v3
	v_lshl_add_u64 v[0:1], s[14:15], 0, v[76:77]
	s_mov_b64 s[6:7], 0x679f000
	v_lshl_add_u64 v[78:79], v[0:1], 0, s[6:7]
	s_mov_b64 s[6:7], 0x24a0000
	v_lshl_add_u64 v[80:81], v[0:1], 0, s[6:7]
	s_add_u32 s6, s14, 0x5dce000
	s_addc_u32 s7, s15, 0
	v_and_b32_e32 v92, 31, v199
	s_add_u32 s10, s14, 0x5c1c800
	v_or_b32_e32 v6, v3, v92
	s_addc_u32 s11, s15, 0
	v_lshl_add_u32 v6, v6, 7, 0
	v_lshl_add_u32 v8, v92, 7, 0
	s_add_u32 s8, s14, 0x879f000
	v_add_u32_e32 v94, 0, v5
	s_mov_b32 s5, 0
	s_addc_u32 s9, s15, 0
	v_add_u32_e32 v95, 0x4000, v94
	s_mov_b64 s[18:19], 0x10000
	v_add_u32_e32 v96, 0x1000, v94
	v_add_u32_e32 v97, 0x5000, v94
	s_mov_b64 s[20:21], 0x20000
	v_add_u32_e32 v98, 0x2000, v94
	v_add_u32_e32 v99, 0x6000, v94
	s_mov_b64 s[22:23], 0x30000
	v_add_u32_e32 v100, 0x3000, v94
	v_add_u32_e32 v101, 0x7000, v94
	s_mov_b64 s[24:25], 0x679f080
	s_mov_b64 s[26:27], 0x24a0080
	v_add_u32_e32 v102, 0x8000, v94
	v_add_u32_e32 v103, 0xc000, v94
	s_mov_b64 s[28:29], 0x67af080
	v_add_u32_e32 v104, 0x9000, v94
	s_mov_b64 s[30:31], 0x24b0080
	v_add_u32_e32 v105, 0xd000, v94
	s_mov_b64 s[34:35], 0x67bf080
	v_add_u32_e32 v106, 0xa000, v94
	s_mov_b64 s[36:37], 0x24c0080
	v_add_u32_e32 v107, 0xe000, v94
	s_mov_b64 s[38:39], 0x67cf080
	v_add_u32_e32 v108, 0xb000, v94
	s_mov_b64 s[40:41], 0x24d0080
	v_add_u32_e32 v109, 0xf000, v94
	v_add_u32_e32 v110, v6, v7
	v_add_u32_e32 v111, v8, v7
	s_waitcnt vmcnt(5)
	v_add_u32_e32 v112, v6, v9
	v_add_u32_e32 v113, v8, v9
	v_add_u32_e32 v114, v6, v10
	v_add_u32_e32 v115, v8, v10
	s_waitcnt vmcnt(4)
	v_add_u32_e32 v116, v6, v2
	v_add_u32_e32 v117, v8, v2
	s_mov_b64 s[42:43], 0x679f100
	s_mov_b64 s[44:45], 0x24a0100
	s_mov_b64 s[46:47], 0x67af100
	s_mov_b64 s[48:49], 0x24b0100
	s_mov_b64 s[50:51], 0x67bf100
	s_mov_b64 s[52:53], 0x24c0100
	s_mov_b64 s[54:55], 0x67cf100
	s_mov_b64 s[56:57], 0x24d0100
	s_movk_i32 s68, 0x1600
	s_mov_b32 s69, 0x10000
	s_mov_b32 s70, 0x20000
	s_mov_b32 s71, 0x30000
	s_mov_b32 s72, 0x40000
	s_mov_b32 s73, 0x50000
	s_mov_b32 s74, 0x60000
	s_mov_b32 s75, 0x70000
	v_mov_b32_e32 v118, 0x358637bd
	s_mov_b32 s39, 0
	s_branch .LBB0_1098

.Lmap_done_1:
	s_lshl_b32 s60, s4, 7
	s_lshl_b32 s58, s76, 7
	s_ashr_i32 s61, s60, 31
	s_ashr_i32 s59, s58, 31
	s_lshl_b64 s[62:63], s[60:61], 11
	s_lshl_b64 s[64:65], s[58:59], 11
	s_cmp_eq_u32 s39, 1
	s_cbranch_scc1 .Lgk_pfhead_p12
	s_lshl_b32 s38, s60, 11
	s_add_u32 s18, s14, s38
	s_addc_u32 s19, s15, 0
	s_add_u32 s18, s18, 0x679f000
	s_addc_u32 s19, s19, 0
	s_add_u32 s20, s18, 0x10000
	s_addc_u32 s21, s19, 0
	s_add_u32 s22, s20, 0x10000
	s_addc_u32 s23, s21, 0
	s_add_u32 s24, s22, 0x10000
	s_addc_u32 s25, s23, 0
	s_lshl_b32 s38, s58, 11
	s_add_u32 s26, s14, s38
	s_addc_u32 s27, s15, 0
	s_add_u32 s26, s26, 0x24a0000
	s_addc_u32 s27, s27, 0
	s_add_u32 s28, s26, 0x10000
	s_addc_u32 s29, s27, 0
	s_add_u32 s30, s28, 0x10000
	s_addc_u32 s31, s29, 0
	s_add_u32 s34, s30, 0x10000
	s_addc_u32 s35, s31, 0
	v_readfirstlane_b32 s36, v94
	v_mov_b32_e32 v254, v76
	s_mov_b32 m0, s36
	s_nop 0
	global_load_lds_dwordx4 v254, s[18:19]
	s_add_u32 m0, m0, 0x1000
	s_nop 0
	global_load_lds_dwordx4 v254, s[20:21]
	s_add_u32 m0, m0, 0x1000
	s_nop 0
	global_load_lds_dwordx4 v254, s[22:23]
	s_add_u32 m0, m0, 0x1000
	s_nop 0
	global_load_lds_dwordx4 v254, s[24:25]
	s_add_u32 m0, m0, 0x1000
	s_nop 0
	global_load_lds_dwordx4 v254, s[26:27]
	s_add_u32 m0, m0, 0x1000
	s_nop 0
	global_load_lds_dwordx4 v254, s[28:29]
	s_add_u32 m0, m0, 0x1000
	s_nop 0
	global_load_lds_dwordx4 v254, s[30:31]
	s_add_u32 m0, m0, 0x1000
	s_nop 0
	global_load_lds_dwordx4 v254, s[34:35]
	v_add_u32_e32 v254, 0x80, v254
	s_add_u32 m0, s36, 0x8000
	s_nop 0
	global_load_lds_dwordx4 v254, s[18:19]
	s_add_u32 m0, m0, 0x1000
	s_nop 0
	global_load_lds_dwordx4 v254, s[20:21]
	s_add_u32 m0, m0, 0x1000
	s_nop 0
	global_load_lds_dwordx4 v254, s[22:23]
	s_add_u32 m0, m0, 0x1000
	s_nop 0
	global_load_lds_dwordx4 v254, s[24:25]
	s_add_u32 m0, m0, 0x1000
	s_nop 0
	global_load_lds_dwordx4 v254, s[26:27]
	s_add_u32 m0, m0, 0x1000
	s_nop 0
	global_load_lds_dwordx4 v254, s[28:29]
	s_add_u32 m0, m0, 0x1000
	s_nop 0
	global_load_lds_dwordx4 v254, s[30:31]
	s_add_u32 m0, m0, 0x1000
	s_nop 0
	global_load_lds_dwordx4 v254, s[34:35]
	v_add_u32_e32 v254, 0x80, v254

.Lmap_done_1_pf_p12:
	s_lshl_b32 s44, s41, 7
	s_lshl_b32 s42, s50, 7
	s_ashr_i32 s45, s44, 31
	s_ashr_i32 s43, s42, 31
	s_lshl_b64 s[46:47], s[44:45], 11
	s_lshl_b64 s[48:49], s[42:43], 11
	s_lshl_b32 s38, s44, 11
	s_add_u32 s18, s14, s38
	s_addc_u32 s19, s15, 0
	s_add_u32 s18, s18, 0x679f000
	s_addc_u32 s19, s19, 0
	s_add_u32 s20, s18, 0x10000
	s_addc_u32 s21, s19, 0
	s_add_u32 s22, s20, 0x10000
	s_addc_u32 s23, s21, 0
	s_add_u32 s24, s22, 0x10000
	s_addc_u32 s25, s23, 0
	s_lshl_b32 s38, s42, 11
	s_add_u32 s26, s14, s38
	s_addc_u32 s27, s15, 0
	s_add_u32 s26, s26, 0x24a0000
	s_addc_u32 s27, s27, 0
	s_add_u32 s28, s26, 0x10000
	s_addc_u32 s29, s27, 0
	s_add_u32 s30, s28, 0x10000
	s_addc_u32 s31, s29, 0
	s_add_u32 s34, s30, 0x10000
	s_addc_u32 s35, s31, 0
	v_mov_b32_e32 v254, v76
	s_mov_b32 s39, 1
	s_waitcnt vmcnt(8)
	s_barrier
	ds_read_b128 v[64:67], v110
	ds_read_b128 v[68:71], v111 offset:16384
	ds_read_b128 v[72:75], v111 offset:20480
	ds_read_b128 v[82:85], v111 offset:24576
	ds_read_b128 v[86:89], v111 offset:28672
	ds_read_b128 v[120:123], v112
	ds_read_b128 v[124:127], v113 offset:16384
	ds_read_b128 v[128:131], v113 offset:20480
	ds_read_b128 v[132:135], v113 offset:24576
	ds_read_b128 v[136:139], v113 offset:28672
	ds_read_b128 v[140:143], v114
	ds_read_b128 v[218:221], v115 offset:16384
	ds_read_b128 v[222:225], v115 offset:20480
	ds_read_b128 v[226:229], v115 offset:24576
	ds_read_b128 v[230:233], v115 offset:28672
	ds_read_b128 v[234:237], v116
	ds_read_b128 v[238:241], v117 offset:16384
	ds_read_b128 v[242:245], v117 offset:20480
	ds_read_b128 v[246:249], v117 offset:24576
	ds_read_b128 v[250:253], v117 offset:28672
	s_waitcnt lgkmcnt(0)
	s_barrier
	s_mov_b32 m0, s36
	s_setprio 1
	v_mfma_f32_32x32x16_bf16 v[48:63], v[64:67], v[68:71], v[48:63]
	v_mfma_f32_32x32x16_bf16 v[32:47], v[64:67], v[72:75], v[32:47]
	global_load_lds_dwordx4 v254, s[18:19]
	s_add_u32 m0, m0, 0x1000
	v_mfma_f32_32x32x16_bf16 v[16:31], v[64:67], v[82:85], v[16:31]
	v_mfma_f32_32x32x16_bf16 v[0:15], v[64:67], v[86:89], v[0:15]
	global_load_lds_dwordx4 v254, s[20:21]
	s_add_u32 m0, m0, 0x1000
	v_mfma_f32_32x32x16_bf16 v[48:63], v[120:123], v[124:127], v[48:63]
	v_mfma_f32_32x32x16_bf16 v[32:47], v[120:123], v[128:131], v[32:47]
	global_load_lds_dwordx4 v254, s[22:23]
	s_add_u32 m0, m0, 0x1000
	v_mfma_f32_32x32x16_bf16 v[16:31], v[120:123], v[132:135], v[16:31]
	v_mfma_f32_32x32x16_bf16 v[0:15], v[120:123], v[136:139], v[0:15]
	global_load_lds_dwordx4 v254, s[24:25]
	s_add_u32 m0, m0, 0x1000
	v_mfma_f32_32x32x16_bf16 v[48:63], v[140:143], v[218:221], v[48:63]
	v_mfma_f32_32x32x16_bf16 v[32:47], v[140:143], v[222:225], v[32:47]
	global_load_lds_dwordx4 v254, s[26:27]
	s_add_u32 m0, m0, 0x1000
	v_mfma_f32_32x32x16_bf16 v[16:31], v[140:143], v[226:229], v[16:31]
	v_mfma_f32_32x32x16_bf16 v[0:15], v[140:143], v[230:233], v[0:15]
	global_load_lds_dwordx4 v254, s[28:29]
	s_add_u32 m0, m0, 0x1000
	v_mfma_f32_32x32x16_bf16 v[48:63], v[234:237], v[238:241], v[48:63]
	v_mfma_f32_32x32x16_bf16 v[32:47], v[234:237], v[242:245], v[32:47]
	global_load_lds_dwordx4 v254, s[30:31]
	s_add_u32 m0, m0, 0x1000
	v_mfma_f32_32x32x16_bf16 v[16:31], v[234:237], v[246:249], v[16:31]
	v_mfma_f32_32x32x16_bf16 v[0:15], v[234:237], v[250:253], v[0:15]
	global_load_lds_dwordx4 v254, s[34:35]
	s_setprio 0
	v_add_u32_e32 v254, 0x80, v254
	s_waitcnt vmcnt(8)
	s_barrier
	ds_read_b128 v[64:67], v110 offset:32768
	ds_read_b128 v[68:71], v111 offset:49152
	ds_read_b128 v[72:75], v111 offset:53248
	ds_read_b128 v[82:85], v111 offset:57344
	ds_read_b128 v[86:89], v111 offset:61440
	ds_read_b128 v[120:123], v112 offset:32768
	ds_read_b128 v[124:127], v113 offset:49152
	ds_read_b128 v[128:131], v113 offset:53248
	ds_read_b128 v[132:135], v113 offset:57344
	ds_read_b128 v[136:139], v113 offset:61440
	ds_read_b128 v[140:143], v114 offset:32768
	ds_read_b128 v[218:221], v115 offset:49152
	ds_read_b128 v[222:225], v115 offset:53248
	ds_read_b128 v[226:229], v115 offset:57344
	ds_read_b128 v[230:233], v115 offset:61440
	ds_read_b128 v[234:237], v116 offset:32768
	ds_read_b128 v[238:241], v117 offset:49152
	ds_read_b128 v[242:245], v117 offset:53248
	ds_read_b128 v[246:249], v117 offset:57344
	ds_read_b128 v[250:253], v117 offset:61440
	s_waitcnt lgkmcnt(0)
	s_barrier
	s_add_u32 m0, s36, 0x8000
	s_setprio 1
	v_mfma_f32_32x32x16_bf16 v[48:63], v[64:67], v[68:71], v[48:63]
	v_mfma_f32_32x32x16_bf16 v[32:47], v[64:67], v[72:75], v[32:47]
	global_load_lds_dwordx4 v254, s[18:19]
	s_add_u32 m0, m0, 0x1000
	v_mfma_f32_32x32x16_bf16 v[16:31], v[64:67], v[82:85], v[16:31]
	v_mfma_f32_32x32x16_bf16 v[0:15], v[64:67], v[86:89], v[0:15]
	global_load_lds_dwordx4 v254, s[20:21]
	s_add_u32 m0, m0, 0x1000
	v_mfma_f32_32x32x16_bf16 v[48:63], v[120:123], v[124:127], v[48:63]
	v_mfma_f32_32x32x16_bf16 v[32:47], v[120:123], v[128:131], v[32:47]
	global_load_lds_dwordx4 v254, s[22:23]
	s_add_u32 m0, m0, 0x1000
	v_mfma_f32_32x32x16_bf16 v[16:31], v[120:123], v[132:135], v[16:31]
	v_mfma_f32_32x32x16_bf16 v[0:15], v[120:123], v[136:139], v[0:15]
	global_load_lds_dwordx4 v254, s[24:25]
	s_add_u32 m0, m0, 0x1000
	v_mfma_f32_32x32x16_bf16 v[48:63], v[140:143], v[218:221], v[48:63]
	v_mfma_f32_32x32x16_bf16 v[32:47], v[140:143], v[222:225], v[32:47]
	global_load_lds_dwordx4 v254, s[26:27]
	s_add_u32 m0, m0, 0x1000
	v_mfma_f32_32x32x16_bf16 v[16:31], v[140:143], v[226:229], v[16:31]
	v_mfma_f32_32x32x16_bf16 v[0:15], v[140:143], v[230:233], v[0:15]
	global_load_lds_dwordx4 v254, s[28:29]
	s_add_u32 m0, m0, 0x1000
	v_mfma_f32_32x32x16_bf16 v[48:63], v[234:237], v[238:241], v[48:63]
	v_mfma_f32_32x32x16_bf16 v[32:47], v[234:237], v[242:245], v[32:47]
	global_load_lds_dwordx4 v254, s[30:31]
	s_add_u32 m0, m0, 0x1000
	v_mfma_f32_32x32x16_bf16 v[16:31], v[234:237], v[246:249], v[16:31]
	v_mfma_f32_32x32x16_bf16 v[0:15], v[234:237], v[250:253], v[0:15]
	global_load_lds_dwordx4 v254, s[34:35]
	s_setprio 0
	v_add_u32_e32 v254, 0x80, v254
	s_branch .LBB0_1097

.LBB0_1102:
	s_cmp_gt_i32 s17, 13
	s_cselect_b64 s[6:7], -1, 0
	s_and_b64 s[0:1], s[0:1], s[6:7]
	s_andn2_b64 vcc, exec, s[0:1]
	s_cbranch_vccnz .LBB0_1114
	s_waitcnt vmcnt(0)
	v_or_b32_e32 v0, v201, v200
	s_movk_i32 s0, 0x3ff
	v_and_or_b32 v0, v0, s0, v199
	v_cmp_eq_u32_e32 vcc, 0, v0
	s_waitcnt lgkmcnt(0)
	s_barrier
	s_and_saveexec_b64 s[0:1], vcc
	s_cbranch_execz .LBB0_1113
	s_add_u32 s4, s14, 0x5be8c00
	s_addc_u32 s5, s15, 0
	s_lshl_b32 s3, s2, 1
	v_mov_b32_e32 v0, s3
	v_mov_b32_e32 v1, 0x930d
	global_store_short v0, v1, s[4:5] sc1
	s_cmp_lg_u32 s2, 0
	s_cbranch_scc1 .Lgbar_wait_12
	s_lshr_b32 s3, s33, 3
	s_bfm_b64 s[8:9], s3, 0
	s_cmpk_gt_u32 s33, 0x1ff
	s_cselect_b64 s[8:9], -1, s[8:9]
	s_mov_b64 exec, -1
	v_mbcnt_lo_u32_b32 v229, -1, 0
	v_mbcnt_hi_u32_b32 v229, -1, v229
	v_lshlrev_b32_e32 v229, 4, v229
	s_mov_b32 s10, 0x930d930d
	s_mov_b64 exec, s[8:9]

.LBB0_1114:
	s_cmp_lt_i32 s16, 14
	s_cselect_b64 s[4:5], -1, 0
	s_and_b64 s[0:1], s[4:5], s[6:7]
	s_andn2_b64 vcc, exec, s[0:1]
	s_cbranch_vccnz .LBB0_1154
	s_ashr_i32 s0, s2, 31
	s_and_b32 s0, s0, s33
	s_add_i32 s3, s0, s2
	s_cmpk_gt_i32 s3, 0x3ff
	s_cbranch_scc1 .LBB0_1154
	s_waitcnt lgkmcnt(0)
	v_lshrrev_b32_e32 v1, 5, v199
	v_bfe_u32 v5, v199, 1, 3
	v_lshrrev_b32_e32 v6, 4, v199
	v_lshrrev_b32_e32 v0, 3, v199
	v_bfe_u32 v2, v199, 5, 1
	v_xor_b32_e32 v7, v6, v199
	v_bitop3_b32 v1, v1, v5, 1 bitop3:0x6c
	v_mul_u32_u24_e32 v3, 0xb00, v0
	v_lshlrev_b32_e32 v7, 3, v7
	v_lshlrev_b32_e32 v9, 4, v1
	v_bitop3_b32 v1, v2, v5, 2 bitop3:0x36
	v_lshrrev_b32_e32 v4, 1, v199
	v_and_or_b32 v7, v7, 56, v3
	v_lshlrev_b32_e32 v11, 4, v1
	v_bitop3_b32 v1, v2, v5, 4 bitop3:0x36
	v_lshlrev_b32_e32 v64, 1, v7
	v_mov_b32_e32 v65, 0
	v_and_b32_e32 v4, 0x1e0, v4
	v_lshlrev_b32_e32 v12, 4, v1
	v_bitop3_b32 v1, v2, v5, 6 bitop3:0x36
	v_lshlrev_b32_e32 v2, 4, v1
	s_waitcnt vmcnt(25)
	v_and_or_b32 v139, v0, 4, v4
	v_lshl_add_u64 v[0:1], s[14:15], 0, v[64:65]
	s_mov_b64 s[8:9], 0x879f000
	v_and_b32_e32 v138, 31, v199
	v_lshl_add_u64 v[66:67], v[0:1], 0, s[8:9]
	s_mov_b64 s[8:9], 0x4b20000
	s_add_u32 s10, s14, 0x5c4e000
	v_lshlrev_b32_e32 v7, 4, v199
	v_or_b32_e32 v8, v4, v138
	v_lshl_add_u64 v[68:69], v[0:1], 0, s[8:9]
	s_addc_u32 s11, s15, 0
	v_bitop3_b32 v0, v6, 7, v199 bitop3:0x48
	v_lshlrev_b32_e32 v1, 1, v3
	v_lshl_add_u32 v8, v8, 7, 0
	v_lshl_add_u32 v10, v138, 7, 0
	s_add_u32 s8, s14, 0x679f000
	v_lshl_or_b32 v64, v0, 4, v1
	v_add_u32_e32 v141, 0, v7
	v_mbcnt_lo_u32_b32 v0, -1, 0
	s_mov_b32 s7, 0
	v_cmp_eq_u32_e64 s[0:1], 0, v138
	s_addc_u32 s9, s15, 0
	v_mov_b32_e32 v140, 0x1600
	v_add_u32_e32 v142, 0x4000, v141
	s_mov_b64 s[18:19], 0x2c000
	v_add_u32_e32 v143, 0x1000, v141
	s_waitcnt vmcnt(24)
	v_add_u32_e32 v144, 0x5000, v141
	s_mov_b64 s[20:21], 0x58000
	v_add_u32_e32 v145, 0x2000, v141
	v_add_u32_e32 v146, 0x6000, v141
	s_mov_b64 s[22:23], 0x84000
	v_add_u32_e32 v147, 0x3000, v141
	v_add_u32_e32 v148, 0x7000, v141
	s_mov_b64 s[24:25], 0x879f080
	s_mov_b64 s[26:27], 0x4b20080
	v_add_u32_e32 v149, 0x8000, v141
	v_add_u32_e32 v150, 0xc000, v141
	s_mov_b64 s[28:29], 0x87cb080
	v_add_u32_e32 v151, 0x9000, v141
	s_mov_b64 s[30:31], 0x4b4c080
	s_waitcnt vmcnt(23)
	v_add_u32_e32 v152, 0xd000, v141
	s_mov_b64 s[34:35], 0x87f7080
	v_add_u32_e32 v153, 0xa000, v141
	s_mov_b64 s[36:37], 0x4b78080
	v_add_u32_e32 v154, 0xe000, v141
	s_mov_b64 s[38:39], 0x8823080
	v_add_u32_e32 v155, 0xb000, v141
	s_mov_b64 s[40:41], 0x4ba4080
	s_waitcnt vmcnt(22)
	v_add_u32_e32 v156, 0xf000, v141
	v_add_u32_e32 v157, v8, v9
	v_add_u32_e32 v158, v10, v9
	v_add_u32_e32 v159, v8, v11
	s_waitcnt vmcnt(21)
	v_add_u32_e32 v160, v10, v11
	v_add_u32_e32 v161, v8, v12
	v_add_u32_e32 v162, v10, v12
	v_add_u32_e32 v163, v8, v2
	s_waitcnt vmcnt(19)
	v_add_u32_e32 v164, v10, v2
	s_mov_b64 s[42:43], 0x879f100
	s_mov_b64 s[44:45], 0x4b20100
	s_mov_b64 s[46:47], 0x87cb100
	s_mov_b64 s[48:49], 0x4b4c100
	s_mov_b64 s[50:51], 0x87f7100
	s_mov_b64 s[52:53], 0x4b78100
	s_mov_b64 s[54:55], 0x8823100
	s_mov_b64 s[56:57], 0x4ba4100
	s_add_i32 s66, 0, 0x12068
	v_mbcnt_hi_u32_b32 v165, -1, v0
	s_mov_b32 s39, 0
	s_branch .LBB0_1118

.LBB0_1118:
	s_ashr_i32 s6, s3, 31
	s_lshr_b32 s6, s6, 26
	s_add_i32 s6, s3, s6
	s_ashr_i32 s58, s6, 6
	s_andn2_b32 s6, s6, 63
	s_sub_i32 s6, s3, s6
	s_ashr_i32 s59, s6, 31
	s_lshr_b32 s59, s59, 29
	s_add_i32 s59, s6, s59
	s_ashr_i32 s64, s59, 3
	s_and_b32 s59, s59, -8
	s_lshl_b32 s58, s58, 3
	s_sub_i32 s6, s6, s59
	s_add_i32 s6, s6, s58
	s_lshl_b32 s67, s6, 7
	s_lshl_b32 s68, s64, 7
	s_waitcnt lgkmcnt(0)
	s_cmp_eq_u32 s39, 1
	s_cbranch_scc1 .Lgk_pfhead_p13
	s_mul_i32 s38, s6, 0xb0000
	s_add_u32 s18, s14, s38
	s_addc_u32 s19, s15, 0
	s_add_u32 s18, s18, 0x879f000
	s_addc_u32 s19, s19, 0
	s_add_u32 s20, s18, 0x2c000
	s_addc_u32 s21, s19, 0
	s_add_u32 s22, s20, 0x2c000
	s_addc_u32 s23, s21, 0
	s_add_u32 s24, s22, 0x2c000
	s_addc_u32 s25, s23, 0
	s_mul_i32 s38, s64, 0xb0000
	s_add_u32 s26, s14, s38
	s_addc_u32 s27, s15, 0
	s_add_u32 s26, s26, 0x4b20000
	s_addc_u32 s27, s27, 0
	s_add_u32 s28, s26, 0x2c000
	s_addc_u32 s29, s27, 0
	s_add_u32 s30, s28, 0x2c000
	s_addc_u32 s31, s29, 0
	s_add_u32 s34, s30, 0x2c000
	s_addc_u32 s35, s31, 0
	v_readfirstlane_b32 s36, v141
	v_mov_b32_e32 v254, v64
	s_mov_b32 m0, s36
	s_nop 0
	global_load_lds_dwordx4 v254, s[18:19]
	s_add_u32 m0, m0, 0x1000
	s_nop 0
	global_load_lds_dwordx4 v254, s[20:21]
	s_add_u32 m0, m0, 0x1000
	s_nop 0
	global_load_lds_dwordx4 v254, s[22:23]
	s_add_u32 m0, m0, 0x1000
	s_nop 0
	global_load_lds_dwordx4 v254, s[24:25]
	s_add_u32 m0, m0, 0x1000
	s_nop 0
	global_load_lds_dwordx4 v254, s[26:27]
	s_add_u32 m0, m0, 0x1000
	s_nop 0
	global_load_lds_dwordx4 v254, s[28:29]
	s_add_u32 m0, m0, 0x1000
	s_nop 0
	global_load_lds_dwordx4 v254, s[30:31]
	s_add_u32 m0, m0, 0x1000
	s_nop 0
	global_load_lds_dwordx4 v254, s[34:35]
	v_add_u32_e32 v254, 0x80, v254
	s_add_u32 m0, s36, 0x8000
	s_nop 0
	global_load_lds_dwordx4 v254, s[18:19]
	s_add_u32 m0, m0, 0x1000
	s_nop 0
	global_load_lds_dwordx4 v254, s[20:21]
	s_add_u32 m0, m0, 0x1000
	s_nop 0
	global_load_lds_dwordx4 v254, s[22:23]
	s_add_u32 m0, m0, 0x1000
	s_nop 0
	global_load_lds_dwordx4 v254, s[24:25]
	s_add_u32 m0, m0, 0x1000
	s_nop 0
	global_load_lds_dwordx4 v254, s[26:27]
	s_add_u32 m0, m0, 0x1000
	s_nop 0
	global_load_lds_dwordx4 v254, s[28:29]
	s_add_u32 m0, m0, 0x1000
	s_nop 0
	global_load_lds_dwordx4 v254, s[30:31]
	s_add_u32 m0, m0, 0x1000
	s_nop 0
	global_load_lds_dwordx4 v254, s[34:35]
	v_add_u32_e32 v254, 0x80, v254

.LBB0_1118_pf_p13:
	s_ashr_i32 s41, s40, 31
	s_lshr_b32 s41, s41, 26
	s_add_i32 s41, s40, s41
	s_ashr_i32 s42, s41, 6
	s_andn2_b32 s41, s41, 63
	s_sub_i32 s41, s40, s41
	s_ashr_i32 s43, s41, 31
	s_lshr_b32 s43, s43, 29
	s_add_i32 s43, s41, s43
	s_ashr_i32 s44, s43, 3
	s_and_b32 s43, s43, -8
	s_lshl_b32 s42, s42, 3
	s_sub_i32 s41, s41, s43
	s_add_i32 s41, s41, s42
	s_lshl_b32 s45, s41, 7
	s_lshl_b32 s46, s44, 7
	s_mul_i32 s38, s41, 0xb0000
	s_add_u32 s18, s14, s38
	s_addc_u32 s19, s15, 0
	s_add_u32 s18, s18, 0x879f000
	s_addc_u32 s19, s19, 0
	s_add_u32 s20, s18, 0x2c000
	s_addc_u32 s21, s19, 0
	s_add_u32 s22, s20, 0x2c000
	s_addc_u32 s23, s21, 0
	s_add_u32 s24, s22, 0x2c000
	s_addc_u32 s25, s23, 0
	s_mul_i32 s38, s44, 0xb0000
	s_add_u32 s26, s14, s38
	s_addc_u32 s27, s15, 0
	s_add_u32 s26, s26, 0x4b20000
	s_addc_u32 s27, s27, 0
	s_add_u32 s28, s26, 0x2c000
	s_addc_u32 s29, s27, 0
	s_add_u32 s30, s28, 0x2c000
	s_addc_u32 s31, s29, 0
	s_add_u32 s34, s30, 0x2c000
	s_addc_u32 s35, s31, 0
	v_mov_b32_e32 v254, v64
	s_mov_b32 s39, 1
	s_waitcnt vmcnt(8)
	s_barrier
	ds_read_b128 v[70:73], v157
	ds_read_b128 v[74:77], v158 offset:16384
	ds_read_b128 v[78:81], v158 offset:20480
	ds_read_b128 v[82:85], v158 offset:24576
	ds_read_b128 v[86:89], v158 offset:28672
	ds_read_b128 v[90:93], v159
	ds_read_b128 v[94:97], v160 offset:16384
	ds_read_b128 v[98:101], v160 offset:20480
	ds_read_b128 v[102:105], v160 offset:24576
	ds_read_b128 v[106:109], v160 offset:28672
	ds_read_b128 v[110:113], v161
	ds_read_b128 v[202:205], v162 offset:16384
	ds_read_b128 v[206:209], v162 offset:20480
	ds_read_b128 v[210:213], v162 offset:24576
	ds_read_b128 v[214:217], v162 offset:28672
	ds_read_b128 v[218:221], v163
	ds_read_b128 v[222:225], v164 offset:16384
	ds_read_b128 v[226:229], v164 offset:20480
	ds_read_b128 v[230:233], v164 offset:24576
	ds_read_b128 v[234:237], v164 offset:28672
	s_waitcnt lgkmcnt(0)
	s_barrier
	s_mov_b32 m0, s36
	s_setprio 1
	v_mfma_f32_32x32x16_bf16 v[48:63], v[70:73], v[74:77], v[48:63]
	v_mfma_f32_32x32x16_bf16 v[32:47], v[70:73], v[78:81], v[32:47]
	global_load_lds_dwordx4 v254, s[18:19]
	s_add_u32 m0, m0, 0x1000
	v_mfma_f32_32x32x16_bf16 v[16:31], v[70:73], v[82:85], v[16:31]
	v_mfma_f32_32x32x16_bf16 v[0:15], v[70:73], v[86:89], v[0:15]
	global_load_lds_dwordx4 v254, s[20:21]
	s_add_u32 m0, m0, 0x1000
	v_mfma_f32_32x32x16_bf16 v[48:63], v[90:93], v[94:97], v[48:63]
	v_mfma_f32_32x32x16_bf16 v[32:47], v[90:93], v[98:101], v[32:47]
	global_load_lds_dwordx4 v254, s[22:23]
	s_add_u32 m0, m0, 0x1000
	v_mfma_f32_32x32x16_bf16 v[16:31], v[90:93], v[102:105], v[16:31]
	v_mfma_f32_32x32x16_bf16 v[0:15], v[90:93], v[106:109], v[0:15]
	global_load_lds_dwordx4 v254, s[24:25]
	s_add_u32 m0, m0, 0x1000
	v_mfma_f32_32x32x16_bf16 v[48:63], v[110:113], v[202:205], v[48:63]
	v_mfma_f32_32x32x16_bf16 v[32:47], v[110:113], v[206:209], v[32:47]
	global_load_lds_dwordx4 v254, s[26:27]
	s_add_u32 m0, m0, 0x1000
	v_mfma_f32_32x32x16_bf16 v[16:31], v[110:113], v[210:213], v[16:31]
	v_mfma_f32_32x32x16_bf16 v[0:15], v[110:113], v[214:217], v[0:15]
	global_load_lds_dwordx4 v254, s[28:29]
	s_add_u32 m0, m0, 0x1000
	v_mfma_f32_32x32x16_bf16 v[48:63], v[218:221], v[222:225], v[48:63]
	v_mfma_f32_32x32x16_bf16 v[32:47], v[218:221], v[226:229], v[32:47]
	global_load_lds_dwordx4 v254, s[30:31]
	s_add_u32 m0, m0, 0x1000
	v_mfma_f32_32x32x16_bf16 v[16:31], v[218:221], v[230:233], v[16:31]
	v_mfma_f32_32x32x16_bf16 v[0:15], v[218:221], v[234:237], v[0:15]
	global_load_lds_dwordx4 v254, s[34:35]
	s_setprio 0
	v_add_u32_e32 v254, 0x80, v254
	s_waitcnt vmcnt(8)
	s_barrier
	ds_read_b128 v[70:73], v157 offset:32768
	ds_read_b128 v[74:77], v158 offset:49152
	ds_read_b128 v[78:81], v158 offset:53248
	ds_read_b128 v[82:85], v158 offset:57344
	ds_read_b128 v[86:89], v158 offset:61440
	ds_read_b128 v[90:93], v159 offset:32768
	ds_read_b128 v[94:97], v160 offset:49152
	ds_read_b128 v[98:101], v160 offset:53248
	ds_read_b128 v[102:105], v160 offset:57344
	ds_read_b128 v[106:109], v160 offset:61440
	ds_read_b128 v[110:113], v161 offset:32768
	ds_read_b128 v[202:205], v162 offset:49152
	ds_read_b128 v[206:209], v162 offset:53248
	ds_read_b128 v[210:213], v162 offset:57344
	ds_read_b128 v[214:217], v162 offset:61440
	ds_read_b128 v[218:221], v163 offset:32768
	ds_read_b128 v[222:225], v164 offset:49152
	ds_read_b128 v[226:229], v164 offset:53248
	ds_read_b128 v[230:233], v164 offset:57344
	ds_read_b128 v[234:237], v164 offset:61440
	s_waitcnt lgkmcnt(0)
	s_barrier
	s_add_u32 m0, s36, 0x8000
	s_setprio 1
	v_mfma_f32_32x32x16_bf16 v[48:63], v[70:73], v[74:77], v[48:63]
	v_mfma_f32_32x32x16_bf16 v[32:47], v[70:73], v[78:81], v[32:47]
	global_load_lds_dwordx4 v254, s[18:19]
	s_add_u32 m0, m0, 0x1000
	v_mfma_f32_32x32x16_bf16 v[16:31], v[70:73], v[82:85], v[16:31]
	v_mfma_f32_32x32x16_bf16 v[0:15], v[70:73], v[86:89], v[0:15]
	global_load_lds_dwordx4 v254, s[20:21]
	s_add_u32 m0, m0, 0x1000
	v_mfma_f32_32x32x16_bf16 v[48:63], v[90:93], v[94:97], v[48:63]
	v_mfma_f32_32x32x16_bf16 v[32:47], v[90:93], v[98:101], v[32:47]
	global_load_lds_dwordx4 v254, s[22:23]
	s_add_u32 m0, m0, 0x1000
	v_mfma_f32_32x32x16_bf16 v[16:31], v[90:93], v[102:105], v[16:31]
	v_mfma_f32_32x32x16_bf16 v[0:15], v[90:93], v[106:109], v[0:15]
	global_load_lds_dwordx4 v254, s[24:25]
	s_add_u32 m0, m0, 0x1000
	v_mfma_f32_32x32x16_bf16 v[48:63], v[110:113], v[202:205], v[48:63]
	v_mfma_f32_32x32x16_bf16 v[32:47], v[110:113], v[206:209], v[32:47]
	global_load_lds_dwordx4 v254, s[26:27]
	s_add_u32 m0, m0, 0x1000
	v_mfma_f32_32x32x16_bf16 v[16:31], v[110:113], v[210:213], v[16:31]
	v_mfma_f32_32x32x16_bf16 v[0:15], v[110:113], v[214:217], v[0:15]
	global_load_lds_dwordx4 v254, s[28:29]
	s_add_u32 m0, m0, 0x1000
	v_mfma_f32_32x32x16_bf16 v[48:63], v[218:221], v[222:225], v[48:63]
	v_mfma_f32_32x32x16_bf16 v[32:47], v[218:221], v[226:229], v[32:47]
	global_load_lds_dwordx4 v254, s[30:31]
	s_add_u32 m0, m0, 0x1000
	v_mfma_f32_32x32x16_bf16 v[16:31], v[218:221], v[230:233], v[16:31]
	v_mfma_f32_32x32x16_bf16 v[0:15], v[218:221], v[234:237], v[0:15]
	global_load_lds_dwordx4 v254, s[34:35]
	s_setprio 0
	v_add_u32_e32 v254, 0x80, v254
	s_branch .LBB0_1122

.LBB0_1122:
	s_add_i32 s58, s67, 0xffffe000
	s_lshr_b32 s58, s58, 12
	s_mulk_i32 s58, 0x1800
	s_addk_i32 s58, 0x1800
	s_cmp_gt_i32 s6, 63
	s_cselect_b32 s62, s58, 0
	s_add_i32 s6, s62, 0x4800
	s_lshl_b64 s[58:59], s[6:7], 2
	s_add_u32 s6, s14, s58
	s_addc_u32 s58, s15, s59
	s_add_u32 s60, s6, 0x5ba5000
	s_addc_u32 s61, s58, 0
	s_add_i32 s6, s62, 0x9000
	s_lshl_b64 s[58:59], s[6:7], 2
	v_mov_b32_e32 v70, s66
	s_add_u32 s6, s14, s58
	ds_read_b64 v[70:71], v70
	s_addc_u32 s69, s15, s59
	s_lshl_b32 s58, s64, 14
	s_add_i32 s58, s58, 0x80000
	s_ashr_i32 s59, s58, 31
	s_lshl_b64 s[58:59], s[58:59], 2
	s_add_u32 s58, s10, s58
	s_waitcnt lgkmcnt(0)
	v_readfirstlane_b32 s63, v70
	s_addc_u32 s59, s11, s59
	v_or_b32_e32 v102, s68, v138
	v_add_u32_e32 v70, s67, v139
	v_readfirstlane_b32 s65, v71
	s_add_u32 s62, s63, 0x2000
	v_ashrrev_i32_e32 v103, 31, v102
	v_lshlrev_b32_e32 v191, 10, v70
	s_addc_u32 s63, s65, 0
	v_lshlrev_b64 v[72:73], 2, v[102:103]
	v_or_b32_e32 v187, 0x400, v191
	v_or_b32_e32 v186, 0x4400, v191
	v_or_b32_e32 v189, 0x4c00, v191
	v_or_b32_e32 v194, 0x6c00, v191
	s_add_u32 s64, s6, 0x5ba1000
	v_lshl_add_u64 v[74:75], s[60:61], 0, v[72:73]
	v_add_u32_e32 v130, v191, v102
	v_add_u32_e32 v132, v187, v102
	v_or_b32_e32 v185, 0x800, v191
	v_or_b32_e32 v184, 0xc00, v191
	v_or_b32_e32 v182, 0x2000, v191
	v_or_b32_e32 v180, 0x2400, v191
	v_or_b32_e32 v71, 0x2800, v191
	v_or_b32_e32 v181, 0x2c00, v191
	v_or_b32_e32 v183, 0x4000, v191
	v_add_u32_e32 v112, v186, v102
	v_or_b32_e32 v188, 0x4800, v191
	v_add_u32_e32 v116, v189, v102
	v_or_b32_e32 v190, 0x6000, v191
	v_or_b32_e32 v192, 0x6400, v191
	v_or_b32_e32 v193, 0x6800, v191
	v_add_u32_e32 v128, v194, v102
	s_addc_u32 s65, s69, 0
	global_load_dword v195, v[74:75], off
	v_lshl_add_u64 v[74:75], s[62:63], 0, v[72:73]
	v_ashrrev_i32_e32 v133, 31, v132
	v_add_u32_e32 v134, v185, v102
	v_add_u32_e32 v136, v184, v102
	v_add_u32_e32 v126, v182, v102
	v_add_u32_e32 v118, v180, v102
	v_add_u32_e32 v110, v71, v102
	v_add_u32_e32 v106, v181, v102
	v_add_u32_e32 v108, v183, v102
	v_ashrrev_i32_e32 v113, 31, v112
	v_add_u32_e32 v114, v188, v102
	v_ashrrev_i32_e32 v117, 31, v116
	v_add_u32_e32 v120, v190, v102
	v_add_u32_e32 v122, v192, v102
	v_add_u32_e32 v124, v193, v102
	v_ashrrev_i32_e32 v129, 31, v128
	v_ashrrev_i32_e32 v131, 31, v130
	v_lshl_add_u64 v[72:73], s[64:65], 0, v[72:73]
	global_load_dword v196, v[74:75], off
	global_load_dword v197, v[72:73], off
	v_lshl_add_u64 v[88:89], v[132:133], 2, s[12:13]
	v_ashrrev_i32_e32 v135, 31, v134
	v_ashrrev_i32_e32 v137, 31, v136
	v_ashrrev_i32_e32 v127, 31, v126
	v_ashrrev_i32_e32 v119, 31, v118
	v_ashrrev_i32_e32 v111, 31, v110
	v_ashrrev_i32_e32 v107, 31, v106
	v_ashrrev_i32_e32 v109, 31, v108
	v_lshl_add_u64 v[86:87], v[112:113], 2, s[12:13]
	v_ashrrev_i32_e32 v115, 31, v114
	v_lshl_add_u64 v[92:93], v[116:117], 2, s[12:13]
	v_ashrrev_i32_e32 v121, 31, v120
	v_ashrrev_i32_e32 v123, 31, v122
	v_ashrrev_i32_e32 v125, 31, v124
	v_lshl_add_u64 v[100:101], v[128:129], 2, s[12:13]
	v_lshl_add_u64 v[104:105], v[130:131], 2, s[12:13]
	v_lshl_add_u64 v[84:85], v[134:135], 2, s[12:13]
	v_lshl_add_u64 v[82:83], v[136:137], 2, s[12:13]
	v_lshl_add_u64 v[78:79], v[126:127], 2, s[12:13]
	v_lshl_add_u64 v[72:73], v[118:119], 2, s[12:13]
	v_lshl_add_u64 v[74:75], v[110:111], 2, s[12:13]
	v_lshl_add_u64 v[76:77], v[106:107], 2, s[12:13]
	v_lshl_add_u64 v[80:81], v[108:109], 2, s[12:13]
	global_load_dword v179, v[88:89], off
	global_load_dword v178, v[84:85], off
	global_load_dword v177, v[82:83], off
	global_load_dword v176, v[78:79], off
	global_load_dword v175, v[72:73], off
	global_load_dword v174, v[74:75], off
	global_load_dword v173, v[76:77], off
	global_load_dword v172, v[80:81], off
	v_lshl_add_u64 v[90:91], v[114:115], 2, s[12:13]
	global_load_dword v171, v[86:87], off
	global_load_dword v169, v[90:91], off
	v_lshl_add_u64 v[94:95], v[120:121], 2, s[12:13]
	v_lshl_add_u64 v[96:97], v[122:123], 2, s[12:13]
	v_lshl_add_u64 v[98:99], v[124:125], 2, s[12:13]
	global_load_dword v170, v[92:93], off
	global_load_dword v168, v[94:95], off
	global_load_dword v167, v[96:97], off
	global_load_dword v166, v[98:99], off
	global_load_dword v103, v[100:101], off
	global_load_dword v198, v[104:105], off
	v_lshl_add_u64 v[110:111], v[110:111], 1, s[8:9]
	v_lshl_add_u64 v[106:107], v[106:107], 1, s[8:9]
	s_waitcnt vmcnt(0)
	v_add_f32_e32 v197, 1.0, v197
	v_mul_f32_e32 v196, v196, v197
	v_fmac_f32_e32 v179, v49, v195
	v_fmac_f32_e32 v178, v50, v195
	v_fmac_f32_e32 v177, v51, v195
	v_fmac_f32_e32 v176, v52, v195
	v_fmac_f32_e32 v175, v53, v195
	v_fmac_f32_e32 v174, v54, v195
	v_fmac_f32_e32 v173, v55, v195
	v_fmac_f32_e32 v172, v56, v195
	v_fmac_f32_e32 v171, v57, v195
	v_fmac_f32_e32 v169, v58, v195
	v_fmac_f32_e32 v170, v59, v195
	v_fmac_f32_e32 v168, v60, v195
	v_fmac_f32_e32 v167, v61, v195
	v_fmac_f32_e32 v166, v62, v195
	v_fmac_f32_e32 v103, v63, v195
	v_fmac_f32_e32 v198, v48, v195
	v_mul_f32_e32 v48, v196, v198
	v_cvt_pk_bf16_f32 v58, v48, s0
	v_or_b32_e32 v48, 32, v102
	v_ashrrev_i32_e32 v49, 31, v48
	v_lshlrev_b64 v[52:53], 2, v[48:49]
	global_store_dword v[88:89], v179, off sc1
	global_store_dword v[84:85], v178, off sc1
	global_store_dword v[82:83], v177, off sc1
	global_store_dword v[78:79], v176, off sc1
	global_store_dword v[72:73], v175, off sc1
	global_store_dword v[74:75], v174, off sc1
	global_store_dword v[76:77], v173, off sc1
	global_store_dword v[80:81], v172, off sc1
	global_store_dword v[86:87], v171, off sc1
	global_store_dword v[90:91], v169, off sc1
	global_store_dword v[92:93], v170, off sc1
	global_store_dword v[94:95], v168, off sc1
	global_store_dword v[96:97], v167, off sc1
	global_store_dword v[98:99], v166, off sc1
	global_store_dword v[100:101], v103, off sc1
	global_store_dword v[104:105], v198, off sc1
	v_lshl_add_u64 v[50:51], v[130:131], 1, s[8:9]
	v_lshl_add_u64 v[56:57], s[64:65], 0, v[52:53]
	global_load_dword v197, v[104:105], off offset:128
	v_lshl_add_u64 v[54:55], s[62:63], 0, v[52:53]
	global_load_dword v130, v[56:57], off
	global_load_dword v131, v[54:55], off
	v_mul_f32_e32 v49, v196, v179
	global_store_short v[50:51], v58, off sc1
	v_lshl_add_u64 v[50:51], s[60:61], 0, v[52:53]
	global_load_dword v195, v[50:51], off
	v_lshl_add_u64 v[50:51], v[132:133], 1, s[8:9]
	v_cvt_pk_bf16_f32 v49, v49, s0
	global_store_short v[50:51], v49, off sc1
	v_mul_f32_e32 v49, v196, v178
	v_lshl_add_u64 v[50:51], v[134:135], 1, s[8:9]
	v_cvt_pk_bf16_f32 v49, v49, s0
	global_store_short v[50:51], v49, off sc1
	v_mul_f32_e32 v49, v196, v177
	v_lshl_add_u64 v[50:51], v[136:137], 1, s[8:9]
	v_cvt_pk_bf16_f32 v49, v49, s0
	global_store_short v[50:51], v49, off sc1
	v_mul_f32_e32 v49, v196, v176
	v_lshl_add_u64 v[50:51], v[126:127], 1, s[8:9]
	v_cvt_pk_bf16_f32 v49, v49, s0
	global_store_short v[50:51], v49, off sc1
	v_mul_f32_e32 v49, v196, v175
	v_lshl_add_u64 v[50:51], v[118:119], 1, s[8:9]
	v_cvt_pk_bf16_f32 v49, v49, s0
	global_load_dword v62, v[84:85], off offset:128
	global_load_dword v60, v[78:79], off offset:128
	global_load_dword v59, v[72:73], off offset:128
	global_load_dword v58, v[74:75], off offset:128
	global_load_dword v56, v[80:81], off offset:128
	global_load_dword v57, v[76:77], off offset:128
	global_load_dword v55, v[86:87], off offset:128
	global_load_dword v61, v[82:83], off offset:128
	global_load_dword v54, v[90:91], off offset:128
	global_load_dword v53, v[92:93], off offset:128
	global_load_dword v52, v[94:95], off offset:128
	v_mul_f32_e32 v63, v196, v174
	global_store_short v[50:51], v49, off sc1
	global_load_dword v51, v[96:97], off offset:128
	v_cvt_pk_bf16_f32 v63, v63, s0
	global_load_dword v50, v[98:99], off offset:128
	global_load_dword v49, v[100:101], off offset:128
	s_waitcnt vmcnt(19)
	v_fmac_f32_e32 v197, v32, v195
	global_store_short v[110:111], v63, off sc1
	global_load_dword v63, v[88:89], off offset:128
	v_mul_f32_e32 v110, v196, v173
	v_cvt_pk_bf16_f32 v110, v110, s0
	global_store_short v[106:107], v110, off sc1
	v_lshl_add_u64 v[106:107], v[108:109], 1, s[8:9]
	v_mul_f32_e32 v108, v196, v172
	v_cvt_pk_bf16_f32 v108, v108, s0
	global_store_short v[106:107], v108, off sc1
	v_mul_f32_e32 v108, v196, v171
	v_lshl_add_u64 v[106:107], v[112:113], 1, s[8:9]
	v_cvt_pk_bf16_f32 v108, v108, s0
	global_store_short v[106:107], v108, off sc1
	v_mul_f32_e32 v108, v196, v169
	v_lshl_add_u64 v[106:107], v[114:115], 1, s[8:9]
	v_cvt_pk_bf16_f32 v108, v108, s0
	global_store_short v[106:107], v108, off sc1
	v_mul_f32_e32 v108, v196, v170
	v_lshl_add_u64 v[106:107], v[116:117], 1, s[8:9]
	v_cvt_pk_bf16_f32 v108, v108, s0
	global_store_short v[106:107], v108, off sc1
	v_mul_f32_e32 v108, v196, v168
	v_lshl_add_u64 v[106:107], v[120:121], 1, s[8:9]
	v_cvt_pk_bf16_f32 v108, v108, s0
	global_store_short v[106:107], v108, off sc1
	v_mul_f32_e32 v108, v196, v167
	v_lshl_add_u64 v[106:107], v[122:123], 1, s[8:9]
	v_cvt_pk_bf16_f32 v108, v108, s0
	global_store_short v[106:107], v108, off sc1
	v_mul_f32_e32 v108, v196, v166
	v_lshl_add_u64 v[106:107], v[124:125], 1, s[8:9]
	v_cvt_pk_bf16_f32 v108, v108, s0
	global_store_short v[106:107], v108, off sc1
	v_mul_f32_e32 v108, v196, v103
	v_lshl_add_u64 v[106:107], v[128:129], 1, s[8:9]
	v_cvt_pk_bf16_f32 v108, v108, s0
	global_store_short v[106:107], v108, off sc1
	v_add_f32_e32 v106, 1.0, v130
	v_mul_f32_e32 v107, v131, v106
	v_add_u32_e32 v108, v191, v48
	v_ashrrev_i32_e32 v109, 31, v108
	v_mul_f32_e32 v32, v107, v197
	s_waitcnt vmcnt(25)
	v_fmac_f32_e32 v62, v34, v195
	s_waitcnt vmcnt(18)
	v_fmac_f32_e32 v61, v35, v195
	v_fmac_f32_e32 v60, v36, v195
	v_fmac_f32_e32 v59, v37, v195
	v_fmac_f32_e32 v58, v38, v195
	v_fmac_f32_e32 v57, v39, v195
	v_fmac_f32_e32 v56, v40, v195
	v_fmac_f32_e32 v55, v41, v195
	s_waitcnt vmcnt(17)
	v_fmac_f32_e32 v54, v42, v195
	s_waitcnt vmcnt(16)
	v_fmac_f32_e32 v53, v43, v195
	s_waitcnt vmcnt(15)
	v_fmac_f32_e32 v52, v44, v195
	s_waitcnt vmcnt(13)
	v_fmac_f32_e32 v51, v45, v195
	s_waitcnt vmcnt(12)
	v_fmac_f32_e32 v50, v46, v195
	s_waitcnt vmcnt(11)
	v_fmac_f32_e32 v49, v47, v195
	global_store_dword v[104:105], v197, off offset:128 sc1
	v_lshl_add_u64 v[108:109], v[108:109], 1, s[8:9]
	v_cvt_pk_bf16_f32 v32, v32, s0
	global_store_dword v[84:85], v62, off offset:128 sc1
	global_store_dword v[82:83], v61, off offset:128 sc1
	global_store_dword v[78:79], v60, off offset:128 sc1
	global_store_dword v[72:73], v59, off offset:128 sc1
	global_store_dword v[74:75], v58, off offset:128 sc1
	global_store_dword v[76:77], v57, off offset:128 sc1
	global_store_dword v[80:81], v56, off offset:128 sc1
	global_store_dword v[86:87], v55, off offset:128 sc1
	global_store_dword v[90:91], v54, off offset:128 sc1
	global_store_dword v[92:93], v53, off offset:128 sc1
	global_store_dword v[94:95], v52, off offset:128 sc1
	global_store_dword v[96:97], v51, off offset:128 sc1
	global_store_dword v[98:99], v50, off offset:128 sc1
	global_store_dword v[100:101], v49, off offset:128 sc1
	global_store_short v[108:109], v32, off sc1
	v_add_u32_e32 v108, v187, v48
	global_load_dword v45, v[88:89], off offset:256
	v_ashrrev_i32_e32 v109, 31, v108
	v_mul_f32_e32 v113, v107, v56
	v_cvt_pk_bf16_f32 v113, v113, s0
	v_mul_f32_e32 v106, v197, v197
	v_fmac_f32_e32 v106, v198, v198
	s_waitcnt vmcnt(26)
	v_fmac_f32_e32 v63, v33, v195
	v_mul_f32_e32 v34, v107, v63
	v_lshl_add_u64 v[32:33], v[108:109], 1, s[8:9]
	v_cvt_pk_bf16_f32 v34, v34, s0
	global_store_short v[32:33], v34, off sc1
	v_add_u32_e32 v32, v185, v48
	v_ashrrev_i32_e32 v33, 31, v32
	v_mul_f32_e32 v34, v107, v62
	v_lshl_add_u64 v[32:33], v[32:33], 1, s[8:9]
	v_cvt_pk_bf16_f32 v34, v34, s0
	global_store_short v[32:33], v34, off sc1
	v_add_u32_e32 v32, v184, v48
	v_ashrrev_i32_e32 v33, 31, v32
	v_mul_f32_e32 v34, v107, v61
	v_lshl_add_u64 v[32:33], v[32:33], 1, s[8:9]
	v_cvt_pk_bf16_f32 v34, v34, s0
	global_store_short v[32:33], v34, off sc1
	v_add_u32_e32 v32, v182, v48
	v_ashrrev_i32_e32 v33, 31, v32
	v_mul_f32_e32 v34, v107, v60
	v_lshl_add_u64 v[32:33], v[32:33], 1, s[8:9]
	v_cvt_pk_bf16_f32 v34, v34, s0
	global_store_short v[32:33], v34, off sc1
	v_add_u32_e32 v32, v180, v48
	v_ashrrev_i32_e32 v33, 31, v32
	v_lshl_add_u64 v[34:35], v[32:33], 1, s[8:9]
	v_mul_f32_e32 v32, v107, v59
	v_cvt_pk_bf16_f32 v42, v32, s0
	v_or_b32_e32 v32, 64, v102
	v_ashrrev_i32_e32 v33, 31, v32
	v_lshlrev_b64 v[36:37], 2, v[32:33]
	global_store_dword v[88:89], v63, off offset:128 sc1
	v_lshl_add_u64 v[40:41], s[64:65], 0, v[36:37]
	v_lshl_add_u64 v[38:39], s[62:63], 0, v[36:37]
	global_load_dword v110, v[40:41], off
	global_load_dword v111, v[38:39], off
	v_mul_f32_e32 v33, v107, v58
	global_store_short v[34:35], v42, off sc1
	v_lshl_add_u64 v[34:35], s[60:61], 0, v[36:37]
	global_load_dword v112, v[34:35], off
	v_add_u32_e32 v34, v71, v48
	v_ashrrev_i32_e32 v35, 31, v34
	v_lshl_add_u64 v[34:35], v[34:35], 1, s[8:9]
	v_cvt_pk_bf16_f32 v33, v33, s0
	global_store_short v[34:35], v33, off sc1
	v_add_u32_e32 v34, v181, v48
	v_ashrrev_i32_e32 v35, 31, v34
	v_mul_f32_e32 v33, v107, v57
	v_lshl_add_u64 v[34:35], v[34:35], 1, s[8:9]
	v_cvt_pk_bf16_f32 v33, v33, s0
	global_load_dword v38, v[90:91], off offset:256
	global_load_dword v37, v[92:93], off offset:256
	global_load_dword v36, v[94:95], off offset:256
	global_load_dword v114, v[104:105], off offset:256
	global_load_dword v47, v[84:85], off offset:256
	global_load_dword v39, v[86:87], off offset:256
	global_load_dword v46, v[82:83], off offset:256
	global_load_dword v44, v[78:79], off offset:256
	global_load_dword v43, v[72:73], off offset:256
	global_load_dword v42, v[74:75], off offset:256
	global_load_dword v40, v[80:81], off offset:256
	global_load_dword v41, v[76:77], off offset:256
	v_add_u32_e32 v108, v183, v48
	global_store_short v[34:35], v33, off sc1
	global_load_dword v35, v[96:97], off offset:256
	v_ashrrev_i32_e32 v109, 31, v108
	global_load_dword v34, v[98:99], off offset:256
	global_load_dword v33, v[100:101], off offset:256
	v_lshl_add_u64 v[108:109], v[108:109], 1, s[8:9]
	global_store_short v[108:109], v113, off sc1
	v_add_u32_e32 v108, v186, v48
	v_ashrrev_i32_e32 v109, 31, v108
	v_mul_f32_e32 v113, v107, v55
	v_lshl_add_u64 v[108:109], v[108:109], 1, s[8:9]
	v_cvt_pk_bf16_f32 v113, v113, s0
	global_store_short v[108:109], v113, off sc1
	v_add_u32_e32 v108, v188, v48
	v_ashrrev_i32_e32 v109, 31, v108
	v_mul_f32_e32 v113, v107, v54
	v_lshl_add_u64 v[108:109], v[108:109], 1, s[8:9]
	v_cvt_pk_bf16_f32 v113, v113, s0
	global_store_short v[108:109], v113, off sc1
	v_add_u32_e32 v108, v189, v48
	v_ashrrev_i32_e32 v109, 31, v108
	v_mul_f32_e32 v113, v107, v53
	v_lshl_add_u64 v[108:109], v[108:109], 1, s[8:9]
	v_cvt_pk_bf16_f32 v113, v113, s0
	global_store_short v[108:109], v113, off sc1
	v_add_u32_e32 v108, v190, v48
	v_ashrrev_i32_e32 v109, 31, v108
	v_mul_f32_e32 v113, v107, v52
	v_lshl_add_u64 v[108:109], v[108:109], 1, s[8:9]
	v_cvt_pk_bf16_f32 v113, v113, s0
	global_store_short v[108:109], v113, off sc1
	v_add_u32_e32 v108, v192, v48
	v_ashrrev_i32_e32 v109, 31, v108
	v_mul_f32_e32 v113, v107, v51
	v_lshl_add_u64 v[108:109], v[108:109], 1, s[8:9]
	v_cvt_pk_bf16_f32 v113, v113, s0
	global_store_short v[108:109], v113, off sc1
	v_add_u32_e32 v108, v193, v48
	v_ashrrev_i32_e32 v109, 31, v108
	v_mul_f32_e32 v113, v107, v50
	v_lshl_add_u64 v[108:109], v[108:109], 1, s[8:9]
	v_cvt_pk_bf16_f32 v113, v113, s0
	global_store_short v[108:109], v113, off sc1
	v_add_u32_e32 v108, v194, v48
	v_ashrrev_i32_e32 v109, 31, v108
	v_mul_f32_e32 v48, v107, v49
	v_lshl_add_u64 v[108:109], v[108:109], 1, s[8:9]
	v_cvt_pk_bf16_f32 v48, v48, s0
	global_store_short v[108:109], v48, off sc1
	v_add_u32_e32 v108, v191, v32
	v_ashrrev_i32_e32 v109, 31, v108
	s_waitcnt vmcnt(28)
	v_add_f32_e32 v48, 1.0, v110
	s_waitcnt vmcnt(27)
	v_mul_f32_e32 v48, v111, v48
	s_waitcnt vmcnt(25)
	v_fmac_f32_e32 v45, v17, v112
	global_store_dword v[88:89], v45, off offset:256 sc1
	s_waitcnt vmcnt(24)
	v_fmac_f32_e32 v38, v26, v112
	s_waitcnt vmcnt(23)
	v_fmac_f32_e32 v37, v27, v112
	s_waitcnt vmcnt(22)
	v_fmac_f32_e32 v36, v28, v112
	s_waitcnt vmcnt(21)
	v_fmac_f32_e32 v114, v16, v112
	s_waitcnt vmcnt(20)
	v_fmac_f32_e32 v47, v18, v112
	v_mul_f32_e32 v18, v48, v114
	v_lshl_add_u64 v[16:17], v[108:109], 1, s[8:9]
	v_cvt_pk_bf16_f32 v18, v18, s0
	global_store_short v[16:17], v18, off sc1
	v_add_u32_e32 v16, v187, v32
	v_ashrrev_i32_e32 v17, 31, v16
	v_mul_f32_e32 v18, v48, v45
	v_lshl_add_u64 v[16:17], v[16:17], 1, s[8:9]
	v_cvt_pk_bf16_f32 v18, v18, s0
	global_store_short v[16:17], v18, off sc1
	v_add_u32_e32 v16, v185, v32
	v_ashrrev_i32_e32 v17, 31, v16
	v_mul_f32_e32 v18, v48, v47
	v_lshl_add_u64 v[16:17], v[16:17], 1, s[8:9]
	v_cvt_pk_bf16_f32 v18, v18, s0
	s_waitcnt vmcnt(20)
	v_fmac_f32_e32 v46, v19, v112
	global_store_short v[16:17], v18, off sc1
	v_add_u32_e32 v16, v184, v32
	v_ashrrev_i32_e32 v17, 31, v16
	v_mul_f32_e32 v18, v48, v46
	v_lshl_add_u64 v[16:17], v[16:17], 1, s[8:9]
	v_cvt_pk_bf16_f32 v18, v18, s0
	global_store_short v[16:17], v18, off sc1
	v_add_u32_e32 v16, v182, v32
	v_ashrrev_i32_e32 v17, 31, v16
	v_lshl_add_u64 v[18:19], v[16:17], 1, s[8:9]
	v_or_b32_e32 v16, 0x60, v102
	v_ashrrev_i32_e32 v17, 31, v16
	s_waitcnt vmcnt(21)
	v_fmac_f32_e32 v44, v20, v112
	s_waitcnt vmcnt(20)
	v_fmac_f32_e32 v43, v21, v112
	s_waitcnt vmcnt(19)
	v_fmac_f32_e32 v42, v22, v112
	s_waitcnt vmcnt(17)
	v_fmac_f32_e32 v41, v23, v112
	v_fmac_f32_e32 v40, v24, v112
	v_fmac_f32_e32 v39, v25, v112
	s_waitcnt vmcnt(15)
	v_fmac_f32_e32 v35, v29, v112
	s_waitcnt vmcnt(14)
	v_fmac_f32_e32 v34, v30, v112
	s_waitcnt vmcnt(13)
	v_fmac_f32_e32 v33, v31, v112
	v_lshlrev_b64 v[20:21], 2, v[16:17]
	global_store_dword v[84:85], v47, off offset:256 sc1
	global_store_dword v[82:83], v46, off offset:256 sc1
	global_store_dword v[78:79], v44, off offset:256 sc1
	global_store_dword v[72:73], v43, off offset:256 sc1
	global_store_dword v[74:75], v42, off offset:256 sc1
	global_store_dword v[76:77], v41, off offset:256 sc1
	global_store_dword v[80:81], v40, off offset:256 sc1
	global_store_dword v[86:87], v39, off offset:256 sc1
	global_store_dword v[90:91], v38, off offset:256 sc1
	global_store_dword v[92:93], v37, off offset:256 sc1
	global_store_dword v[94:95], v36, off offset:256 sc1
	global_store_dword v[96:97], v35, off offset:256 sc1
	global_store_dword v[98:99], v34, off offset:256 sc1
	global_store_dword v[100:101], v33, off offset:256 sc1
	global_store_dword v[104:105], v114, off offset:256 sc1
	v_mul_f32_e32 v26, v48, v44
	v_lshl_add_u64 v[22:23], s[62:63], 0, v[20:21]
	v_lshl_add_u64 v[24:25], s[64:65], 0, v[20:21]
	global_load_dword v29, v[104:105], off offset:384
	global_load_dword v17, v[24:25], off
	global_load_dword v30, v[22:23], off
	v_cvt_pk_bf16_f32 v22, v26, s0
	global_store_short v[18:19], v22, off sc1
	v_lshl_add_u64 v[18:19], s[60:61], 0, v[20:21]
	global_load_dword v102, v[18:19], off
	v_add_u32_e32 v18, v180, v32
	v_ashrrev_i32_e32 v19, 31, v18
	v_mul_f32_e32 v20, v48, v43
	v_lshl_add_u64 v[18:19], v[18:19], 1, s[8:9]
	v_cvt_pk_bf16_f32 v20, v20, s0
	global_store_short v[18:19], v20, off sc1
	v_add_u32_e32 v18, v71, v32
	v_ashrrev_i32_e32 v19, 31, v18
	v_mul_f32_e32 v20, v48, v42
	v_lshl_add_u64 v[18:19], v[18:19], 1, s[8:9]
	v_cvt_pk_bf16_f32 v20, v20, s0
	global_store_short v[18:19], v20, off sc1
	v_add_u32_e32 v18, v181, v32
	v_ashrrev_i32_e32 v19, 31, v18
	v_mul_f32_e32 v20, v48, v41
	v_lshl_add_u64 v[18:19], v[18:19], 1, s[8:9]
	v_cvt_pk_bf16_f32 v20, v20, s0
	global_store_short v[18:19], v20, off sc1
	v_add_u32_e32 v18, v183, v32
	v_ashrrev_i32_e32 v19, 31, v18
	v_mul_f32_e32 v20, v48, v40
	v_lshl_add_u64 v[18:19], v[18:19], 1, s[8:9]
	v_cvt_pk_bf16_f32 v20, v20, s0
	global_store_short v[18:19], v20, off sc1
	v_add_u32_e32 v18, v186, v32
	v_ashrrev_i32_e32 v19, 31, v18
	v_mul_f32_e32 v20, v48, v39
	v_lshl_add_u64 v[18:19], v[18:19], 1, s[8:9]
	v_cvt_pk_bf16_f32 v20, v20, s0
	global_store_short v[18:19], v20, off sc1
	v_add_u32_e32 v18, v188, v32
	v_ashrrev_i32_e32 v19, 31, v18
	v_mul_f32_e32 v20, v48, v38
	v_lshl_add_u64 v[18:19], v[18:19], 1, s[8:9]
	v_cvt_pk_bf16_f32 v20, v20, s0
	global_store_short v[18:19], v20, off sc1
	v_add_u32_e32 v18, v189, v32
	v_ashrrev_i32_e32 v19, 31, v18
	v_mul_f32_e32 v20, v48, v37
	v_lshl_add_u64 v[18:19], v[18:19], 1, s[8:9]
	v_cvt_pk_bf16_f32 v20, v20, s0
	global_store_short v[18:19], v20, off sc1
	v_add_u32_e32 v18, v190, v32
	v_ashrrev_i32_e32 v19, 31, v18
	v_mul_f32_e32 v20, v48, v36
	v_lshl_add_u64 v[18:19], v[18:19], 1, s[8:9]
	v_cvt_pk_bf16_f32 v20, v20, s0
	global_store_short v[18:19], v20, off sc1
	v_add_u32_e32 v18, v192, v32
	v_ashrrev_i32_e32 v19, 31, v18
	v_mul_f32_e32 v20, v48, v35
	v_lshl_add_u64 v[18:19], v[18:19], 1, s[8:9]
	v_cvt_pk_bf16_f32 v20, v20, s0
	global_load_dword v28, v[88:89], off offset:384
	global_load_dword v27, v[84:85], off offset:384
	global_load_dword v25, v[78:79], off offset:384
	global_load_dword v24, v[72:73], off offset:384
	global_load_dword v23, v[74:75], off offset:384
	global_load_dword v21, v[80:81], off offset:384
	global_load_dword v22, v[76:77], off offset:384
	v_fmac_f32_e32 v106, v114, v114
	global_store_short v[18:19], v20, off sc1
	v_add_u32_e32 v18, v193, v32
	v_ashrrev_i32_e32 v19, 31, v18
	v_mul_f32_e32 v20, v48, v34
	v_lshl_add_u64 v[18:19], v[18:19], 1, s[8:9]
	v_cvt_pk_bf16_f32 v20, v20, s0
	global_store_short v[18:19], v20, off sc1
	v_add_u32_e32 v18, v194, v32
	v_ashrrev_i32_e32 v19, 31, v18
	v_mul_f32_e32 v20, v48, v33
	v_lshl_add_u64 v[18:19], v[18:19], 1, s[8:9]
	v_cvt_pk_bf16_f32 v20, v20, s0
	global_store_short v[18:19], v20, off sc1
	global_load_dword v20, v[86:87], off offset:384
	s_waitcnt vmcnt(22)
	v_add_f32_e32 v17, 1.0, v17
	global_load_dword v26, v[82:83], off offset:384
	s_waitcnt vmcnt(22)
	v_mul_f32_e32 v32, v30, v17
	v_add_u32_e32 v18, v191, v16
	s_waitcnt vmcnt(20)
	v_fmac_f32_e32 v29, v0, v102
	v_ashrrev_i32_e32 v19, 31, v18
	v_mul_f32_e32 v0, v32, v29
	v_lshl_add_u64 v[18:19], v[18:19], 1, s[8:9]
	v_cvt_pk_bf16_f32 v0, v0, s0
	global_store_short v[18:19], v0, off sc1
	global_load_dword v19, v[90:91], off offset:384
	v_add_u32_e32 v30, v187, v16
	global_load_dword v18, v[92:93], off offset:384
	v_ashrrev_i32_e32 v31, 31, v30
	v_fmac_f32_e32 v106, v29, v29
	global_store_dword v[104:105], v29, off offset:384 sc1
	s_waitcnt vmcnt(15)
	v_fmac_f32_e32 v28, v1, v102
	v_mul_f32_e32 v17, v32, v28
	v_lshl_add_u64 v[0:1], v[30:31], 1, s[8:9]
	v_cvt_pk_bf16_f32 v17, v17, s0
	global_store_short v[0:1], v17, off sc1
	v_add_u32_e32 v0, v185, v16
	s_waitcnt vmcnt(15)
	v_fmac_f32_e32 v27, v2, v102
	global_load_dword v17, v[94:95], off offset:384
	v_ashrrev_i32_e32 v1, 31, v0
	v_mul_f32_e32 v2, v32, v27
	v_lshl_add_u64 v[0:1], v[0:1], 1, s[8:9]
	v_cvt_pk_bf16_f32 v2, v2, s0
	global_store_short v[0:1], v2, off sc1
	v_add_u32_e32 v0, v184, v16
	global_load_dword v2, v[96:97], off offset:384
	v_ashrrev_i32_e32 v1, 31, v0
	v_lshl_add_u64 v[0:1], v[0:1], 1, s[8:9]
	v_add_u32_e32 v30, v182, v16
	s_waitcnt vmcnt(17)
	v_fmac_f32_e32 v25, v4, v102
	v_ashrrev_i32_e32 v31, 31, v30
	v_lshl_add_u64 v[30:31], v[30:31], 1, s[8:9]
	s_waitcnt vmcnt(16)
	v_fmac_f32_e32 v24, v5, v102
	s_waitcnt vmcnt(15)
	v_fmac_f32_e32 v23, v6, v102
	s_waitcnt vmcnt(8)
	v_fmac_f32_e32 v26, v3, v102
	v_mul_f32_e32 v3, v32, v26
	v_cvt_pk_bf16_f32 v3, v3, s0
	global_store_short v[0:1], v3, off sc1
	global_load_dword v1, v[98:99], off offset:384
	v_mul_f32_e32 v0, v32, v25
	v_cvt_pk_bf16_f32 v0, v0, s0
	global_store_short v[30:31], v0, off sc1
	global_load_dword v0, v[100:101], off offset:384
	v_add_u32_e32 v30, v180, v16
	v_ashrrev_i32_e32 v31, 31, v30
	v_mul_f32_e32 v3, v32, v24
	v_lshl_add_u64 v[4:5], v[30:31], 1, s[8:9]
	v_cvt_pk_bf16_f32 v3, v3, s0
	global_store_short v[4:5], v3, off sc1
	v_add_u32_e32 v4, v71, v16
	v_ashrrev_i32_e32 v5, 31, v4
	v_mul_f32_e32 v3, v32, v23
	v_lshl_add_u64 v[4:5], v[4:5], 1, s[8:9]
	v_cvt_pk_bf16_f32 v3, v3, s0
	global_store_short v[4:5], v3, off sc1
	v_add_u32_e32 v4, v181, v16
	v_fmac_f32_e32 v22, v7, v102
	v_ashrrev_i32_e32 v5, 31, v4
	v_mul_f32_e32 v3, v32, v22
	v_lshl_add_u64 v[4:5], v[4:5], 1, s[8:9]
	v_cvt_pk_bf16_f32 v3, v3, s0
	global_store_short v[4:5], v3, off sc1
	v_add_u32_e32 v4, v183, v16
	v_fmac_f32_e32 v21, v8, v102
	v_ashrrev_i32_e32 v5, 31, v4
	v_mul_f32_e32 v3, v32, v21
	v_lshl_add_u64 v[4:5], v[4:5], 1, s[8:9]
	v_cvt_pk_bf16_f32 v3, v3, s0
	global_store_short v[4:5], v3, off sc1
	v_add_u32_e32 v4, v186, v16
	v_fmac_f32_e32 v20, v9, v102
	v_ashrrev_i32_e32 v5, 31, v4
	v_mul_f32_e32 v3, v32, v20
	v_lshl_add_u64 v[4:5], v[4:5], 1, s[8:9]
	v_cvt_pk_bf16_f32 v3, v3, s0
	global_store_short v[4:5], v3, off sc1
	v_add_u32_e32 v4, v188, v16
	s_waitcnt vmcnt(15)
	v_fmac_f32_e32 v19, v10, v102
	v_ashrrev_i32_e32 v5, 31, v4
	v_mul_f32_e32 v3, v32, v19
	v_lshl_add_u64 v[4:5], v[4:5], 1, s[8:9]
	v_cvt_pk_bf16_f32 v3, v3, s0
	global_store_short v[4:5], v3, off sc1
	v_add_u32_e32 v4, v189, v16
	s_waitcnt vmcnt(15)
	v_fmac_f32_e32 v18, v11, v102
	v_ashrrev_i32_e32 v5, 31, v4
	v_mul_f32_e32 v3, v32, v18
	v_lshl_add_u64 v[4:5], v[4:5], 1, s[8:9]
	v_cvt_pk_bf16_f32 v3, v3, s0
	global_store_short v[4:5], v3, off sc1
	v_add_u32_e32 v4, v190, v16
	v_ashrrev_i32_e32 v5, 31, v4
	v_lshl_add_u64 v[4:5], v[4:5], 1, s[8:9]
	v_ashrrev_i32_e32 v71, 31, v70
	global_store_dword v[88:89], v28, off offset:384 sc1
	global_store_dword v[84:85], v27, off offset:384 sc1
	global_store_dword v[82:83], v26, off offset:384 sc1
	global_store_dword v[78:79], v25, off offset:384 sc1
	s_waitcnt vmcnt(17)
	v_fmac_f32_e32 v17, v12, v102
	v_mul_f32_e32 v3, v32, v17
	v_cvt_pk_bf16_f32 v3, v3, s0
	global_store_short v[4:5], v3, off sc1
	v_add_u32_e32 v4, v192, v16
	v_ashrrev_i32_e32 v5, 31, v4
	v_lshl_add_u64 v[4:5], v[4:5], 1, s[8:9]
	s_waitcnt vmcnt(16)
	v_fmac_f32_e32 v2, v13, v102
	v_mul_f32_e32 v3, v32, v2
	v_cvt_pk_bf16_f32 v3, v3, s0
	global_store_short v[4:5], v3, off sc1
	v_add_u32_e32 v4, v193, v16
	v_ashrrev_i32_e32 v5, 31, v4
	v_lshl_add_u64 v[4:5], v[4:5], 1, s[8:9]
	v_xor_b32_e32 v12, 16, v165
	global_store_dword v[72:73], v24, off offset:384 sc1
	global_store_dword v[74:75], v23, off offset:384 sc1
	global_store_dword v[76:77], v22, off offset:384 sc1
	global_store_dword v[80:81], v21, off offset:384 sc1
	global_store_dword v[86:87], v20, off offset:384 sc1
	s_waitcnt vmcnt(20)
	v_fmac_f32_e32 v1, v14, v102
	v_mul_f32_e32 v3, v32, v1
	v_cvt_pk_bf16_f32 v3, v3, s0
	global_store_short v[4:5], v3, off sc1
	v_add_u32_e32 v4, v194, v16
	v_ashrrev_i32_e32 v5, 31, v4
	v_lshl_add_u64 v[10:11], v[4:5], 1, s[8:9]
	v_and_b32_e32 v4, 64, v165
	v_xor_b32_e32 v3, 1, v165
	v_add_u32_e32 v7, 64, v4
	v_cmp_lt_i32_e32 vcc, v3, v7
	v_xor_b32_e32 v4, 2, v165
	s_waitcnt vmcnt(19)
	v_fmac_f32_e32 v0, v15, v102
	v_cndmask_b32_e32 v3, v165, v3, vcc
	v_lshlrev_b32_e32 v3, 2, v3
	ds_bpermute_b32 v5, v3, v106
	v_cmp_lt_i32_e32 vcc, v4, v7
	global_store_dword v[90:91], v19, off offset:384 sc1
	global_store_dword v[92:93], v18, off offset:384 sc1
	v_cndmask_b32_e32 v4, v165, v4, vcc
	v_lshlrev_b32_e32 v4, 2, v4
	s_waitcnt lgkmcnt(0)
	v_add_f32_e32 v6, v106, v5
	ds_bpermute_b32 v8, v4, v6
	v_xor_b32_e32 v5, 4, v165
	v_cmp_lt_i32_e32 vcc, v5, v7
	global_store_dword v[94:95], v17, off offset:384 sc1
	global_store_dword v[96:97], v2, off offset:384 sc1
	v_cndmask_b32_e32 v5, v165, v5, vcc
	v_lshlrev_b32_e32 v5, 2, v5
	s_waitcnt lgkmcnt(0)
	v_add_f32_e32 v8, v6, v8
	ds_bpermute_b32 v9, v5, v8
	v_xor_b32_e32 v6, 8, v165
	v_cmp_lt_i32_e32 vcc, v6, v7
	global_store_dword v[98:99], v1, off offset:384 sc1
	global_store_dword v[100:101], v0, off offset:384 sc1
	v_cndmask_b32_e32 v6, v165, v6, vcc
	v_lshlrev_b32_e32 v6, 2, v6
	s_waitcnt lgkmcnt(0)
	v_add_f32_e32 v8, v8, v9
	ds_bpermute_b32 v9, v6, v8
	v_cmp_lt_i32_e32 vcc, v12, v7
	s_waitcnt lgkmcnt(0)
	v_add_f32_e32 v8, v8, v9
	v_cndmask_b32_e32 v7, v165, v12, vcc
	v_lshlrev_b32_e32 v7, 2, v7
	ds_bpermute_b32 v9, v7, v8
	v_mul_f32_e32 v12, v32, v0
	v_cvt_pk_bf16_f32 v12, v12, s0
	global_store_short v[10:11], v12, off sc1
	s_and_saveexec_b64 s[60:61], s[0:1]
	s_cbranch_execz .LBB0_1124
	s_waitcnt lgkmcnt(0)
	v_add_f32_e32 v10, v8, v9
	v_lshl_add_u64 v[8:9], v[70:71], 2, s[58:59]
	global_store_dword v[8:9], v10, off sc1

.LBB0_1154:
	s_cmp_gt_i32 s17, 14
	s_cselect_b64 s[0:1], -1, 0
	s_and_b64 s[4:5], s[4:5], s[0:1]
	s_andn2_b64 vcc, exec, s[4:5]
	s_cbranch_vccnz .LBB0_1166
	s_waitcnt vmcnt(0)
	v_or_b32_e32 v0, v201, v200
	s_movk_i32 s3, 0x3ff
	v_and_or_b32 v0, v0, s3, v199
	v_cmp_eq_u32_e32 vcc, 0, v0
	s_waitcnt lgkmcnt(0)
	s_barrier
	s_and_saveexec_b64 s[4:5], vcc
	s_cbranch_execz .LBB0_1165
	s_add_u32 s6, s14, 0x5be8c00
	s_addc_u32 s7, s15, 0
	s_lshl_b32 s3, s2, 1
	v_mov_b32_e32 v0, s3
	v_mov_b32_e32 v1, 0x930e
	global_store_short v0, v1, s[6:7] sc1
	s_cmp_lg_u32 s2, 0
	s_cbranch_scc1 .Lgbar_wait_13
	s_lshr_b32 s3, s33, 3
	s_bfm_b64 s[8:9], s3, 0
	s_cmpk_gt_u32 s33, 0x1ff
	s_cselect_b64 s[8:9], -1, s[8:9]
	s_mov_b64 exec, -1
	v_mbcnt_lo_u32_b32 v229, -1, 0
	v_mbcnt_hi_u32_b32 v229, -1, v229
	v_lshlrev_b32_e32 v229, 4, v229
	s_mov_b32 s10, 0x930e930e
	s_mov_b64 exec, s[8:9]

.LBB0_1166:
	s_cmp_lt_i32 s16, 15
	s_cselect_b64 s[6:7], -1, 0
	s_and_b64 s[0:1], s[6:7], s[0:1]
	s_andn2_b64 vcc, exec, s[0:1]
	s_cbranch_vccnz .LBB0_1270
	s_ashr_i32 s0, s2, 31
	s_and_b32 s0, s0, s33
	s_add_i32 s3, s0, s2
	s_cmpk_gt_i32 s3, 0x5ff
	s_cbranch_scc1 .LBB0_1254
	s_waitcnt lgkmcnt(0)
	v_lshrrev_b32_e32 v1, 5, v199
	v_bfe_u32 v4, v199, 1, 3
	s_add_u32 s18, s14, 0x5e4e000
	v_bfe_u32 v2, v199, 5, 1
	v_bitop3_b32 v1, v1, v4, 1 bitop3:0x6c
	s_addc_u32 s19, s15, 0
	v_lshrrev_b32_e32 v0, 3, v199
	v_lshlrev_b32_e32 v5, 4, v199
	s_waitcnt vmcnt(1)
	v_lshlrev_b32_e32 v128, 4, v1
	v_bitop3_b32 v1, v2, v4, 2 bitop3:0x36
	s_add_u32 s10, s14, 0x5bfa000
	v_lshrrev_b32_e32 v3, 1, v199
	v_xor_b32_e32 v6, v5, v199
	v_lshlrev_b32_e32 v7, 11, v0
	s_movk_i32 s0, 0x70
	v_mov_b32_e32 v107, 0
	v_lshlrev_b32_e32 v130, 4, v1
	v_bitop3_b32 v1, v2, v4, 4 bitop3:0x36
	s_addc_u32 s11, s15, 0
	v_and_or_b32 v110, v6, s0, v7
	v_mov_b32_e32 v111, v107
	v_and_b32_e32 v3, 0x1e0, v3
	v_lshlrev_b32_e32 v131, 4, v1
	v_bitop3_b32 v1, v2, v4, 6 bitop3:0x36
	s_add_u32 s20, s14, 0x1111f000
	v_and_b32_e32 v108, 31, v199
	s_waitcnt vmcnt(0)
	v_lshlrev_b32_e32 v132, 4, v1
	v_and_or_b32 v133, v0, 4, v3
	v_lshl_add_u64 v[0:1], s[14:15], 0, v[110:111]
	s_mov_b64 s[0:1], 0x679f000
	s_addc_u32 s21, s15, 0
	v_lshl_add_u64 v[112:113], v[0:1], 0, s[0:1]
	s_mov_b64 s[0:1], 0xda0000
	s_add_u32 s22, s12, 0x9200000
	v_lshlrev_b32_e32 v106, 2, v108
	v_lshl_add_u64 v[114:115], v[0:1], 0, s[0:1]
	s_addc_u32 s23, s13, 0
	v_lshl_add_u64 v[0:1], s[12:13], 0, v[106:107]
	s_mov_b64 s[0:1], 0x8a00000
	v_or_b32_e32 v6, v3, v108
	v_or_b32_e32 v135, 32, v108
	v_or_b32_e32 v137, 64, v108
	v_or_b32_e32 v139, 0x60, v108
	s_add_u32 s24, s14, 0x619f000
	v_lshl_add_u64 v[116:117], v[0:1], 0, s[0:1]
	v_add_u32_e32 v156, 0, v5
	v_mbcnt_lo_u32_b32 v0, -1, 0
	s_mov_b32 s9, 0
	v_lshl_add_u32 v109, v6, 7, 0
	v_lshl_add_u32 v129, v108, 7, 0
	v_lshlrev_b32_e32 v134, 8, v108
	v_lshlrev_b32_e32 v136, 8, v135
	v_lshlrev_b32_e32 v138, 8, v137
	v_lshlrev_b32_e32 v140, 8, v139
	v_or_b32_e32 v141, 1, v133
	v_or_b32_e32 v142, 2, v133
	v_or_b32_e32 v143, 3, v133
	v_or_b32_e32 v144, 8, v133
	v_or_b32_e32 v145, 9, v133
	v_or_b32_e32 v146, 10, v133
	v_or_b32_e32 v147, 11, v133
	v_or_b32_e32 v148, 16, v133
	v_or_b32_e32 v149, 17, v133
	v_or_b32_e32 v150, 18, v133
	v_or_b32_e32 v151, 19, v133
	v_or_b32_e32 v152, 24, v133
	v_or_b32_e32 v153, 25, v133
	v_or_b32_e32 v154, 26, v133
	v_or_b32_e32 v155, 27, v133
	s_addc_u32 s25, s15, 0
	v_add_u32_e32 v157, 0x4000, v156
	s_mov_b64 s[26:27], 0x10000
	v_add_u32_e32 v158, 0x1000, v156
	v_add_u32_e32 v159, 0x5000, v156
	s_mov_b64 s[28:29], 0x20000
	v_add_u32_e32 v160, 0x2000, v156
	v_add_u32_e32 v161, 0x6000, v156
	s_mov_b64 s[30:31], 0x30000
	v_add_u32_e32 v162, 0x3000, v156
	v_add_u32_e32 v163, 0x7000, v156
	s_mov_b64 s[34:35], 0x679f080
	s_mov_b64 s[36:37], 0xda0080
	v_add_u32_e32 v164, 0x8000, v156
	v_add_u32_e32 v165, 0xc000, v156
	s_mov_b64 s[38:39], 0x67af080
	s_mov_b64 s[40:41], 0xdb0080
	s_mov_b64 s[42:43], 0x67bf080
	s_mov_b64 s[44:45], 0xdc0080
	s_mov_b64 s[46:47], 0x67cf080
	s_mov_b64 s[48:49], 0xdd0080
	s_mov_b64 s[50:51], 0x679f100
	s_mov_b64 s[52:53], 0xda0100
	s_mov_b64 s[54:55], 0x67af100
	s_mov_b64 s[56:57], 0xdb0100
	s_mov_b64 s[58:59], 0x67bf100
	s_mov_b64 s[60:61], 0xdc0100
	s_mov_b64 s[62:63], 0x67cf100
	s_mov_b64 s[64:65], 0xdd0100
	s_movk_i32 s74, 0x1100
	s_mov_b32 s75, 0x10000
	s_mov_b32 s76, 0x20000
	s_mov_b32 s77, 0x30000
	s_mov_b32 s78, 0x40000
	s_mov_b32 s79, 0x50000
	s_mov_b32 s80, 0x60000
	s_mov_b32 s81, 0x70000
	v_mov_b32_e32 v166, 0x358637bd
	s_add_i32 s82, 0, 0x120f0
	s_mov_b32 s83, 0x879f000
	v_add_u32_e32 v167, 0x9000, v156
	v_add_u32_e32 v168, 0xd000, v156
	v_add_u32_e32 v169, 0xa000, v156
	v_mbcnt_hi_u32_b32 v170, -1, v0
	s_mov_b32 s49, 0
	s_branch .LBB0_1171
.LBB0_1169:
	v_add_u32_e32 v2, s8, v155
	v_lshlrev_b32_e32 v2, s68, v2
	v_ashrrev_i32_e32 v3, 31, v2
	v_lshl_add_u64 v[2:3], v[2:3], 1, v[28:29]
	v_cvt_pk_bf16_f32 v5, v5, s0
	v_cvt_pk_bf16_f32 v4, v4, s0
	v_cvt_pk_bf16_f32 v1, v1, s0
	v_cvt_pk_bf16_f32 v0, v0, s0
	global_store_short v[2:3], v5, off sc1
	global_store_short v[2:3], v4, off offset:64 sc1
	global_store_short v[2:3], v1, off offset:128 sc1
	global_store_short v[2:3], v0, off offset:192 sc1

.LBB0_1171:
	s_mul_hi_i32 s0, s3, 0x2aaaaaab
	s_lshr_b32 s1, s0, 31
	s_ashr_i32 s0, s0, 4
	s_add_i32 s0, s0, s1
	s_mul_i32 s85, s0, 0xffffffa0
	s_add_i32 s85, s85, s3
	s_lshl_b32 s1, s0, 3
	s_ashr_i32 s0, s85, 31
	s_lshr_b32 s0, s0, 29
	s_add_i32 s0, s85, s0
	s_ashr_i32 s84, s0, 3
	s_and_b32 s0, s0, -8
	s_sub_i32 s8, s85, s0
	s_add_i32 s8, s8, s1
	s_lshl_b32 s66, s8, 7
	s_lshl_b32 s4, s84, 7
	s_ashr_i32 s67, s66, 31
	s_ashr_i32 s5, s4, 31
	s_lshl_b64 s[0:1], s[66:67], 11
	s_lshl_b64 s[68:69], s[4:5], 11
	s_cmp_eq_u32 s49, 1
	s_cbranch_scc1 .Lgk_pfhead_p14
	s_lshl_b32 s48, s66, 11
	s_add_u32 s28, s14, s48
	s_addc_u32 s29, s15, 0
	s_add_u32 s28, s28, 0x679f000
	s_addc_u32 s29, s29, 0
	s_add_u32 s30, s28, 0x10000
	s_addc_u32 s31, s29, 0
	s_add_u32 s34, s30, 0x10000
	s_addc_u32 s35, s31, 0
	s_add_u32 s36, s34, 0x10000
	s_addc_u32 s37, s35, 0
	s_lshl_b32 s48, s4, 11
	s_add_u32 s38, s14, s48
	s_addc_u32 s39, s15, 0
	s_add_u32 s38, s38, 0xda0000
	s_addc_u32 s39, s39, 0
	s_add_u32 s40, s38, 0x10000
	s_addc_u32 s41, s39, 0
	s_add_u32 s42, s40, 0x10000
	s_addc_u32 s43, s41, 0
	s_add_u32 s44, s42, 0x10000
	s_addc_u32 s45, s43, 0
	v_add_u32_e32 v255, v109, v128
	v_add_u32_e32 v157, v129, v128
	v_add_u32_e32 v162, v109, v130
	v_add_u32_e32 v163, v129, v130
	v_add_u32_e32 v164, v109, v131
	v_add_u32_e32 v165, v129, v131
	v_add_u32_e32 v167, v109, v132
	v_add_u32_e32 v168, v129, v132
	v_readfirstlane_b32 s46, v156
	v_mov_b32_e32 v254, v110
	s_mov_b32 m0, s46
	s_nop 0
	global_load_lds_dwordx4 v254, s[28:29]
	s_add_u32 m0, m0, 0x1000
	s_nop 0
	global_load_lds_dwordx4 v254, s[30:31]
	s_add_u32 m0, m0, 0x1000
	s_nop 0
	global_load_lds_dwordx4 v254, s[34:35]
	s_add_u32 m0, m0, 0x1000
	s_nop 0
	global_load_lds_dwordx4 v254, s[36:37]
	s_add_u32 m0, m0, 0x1000
	s_nop 0
	global_load_lds_dwordx4 v254, s[38:39]
	s_add_u32 m0, m0, 0x1000
	s_nop 0
	global_load_lds_dwordx4 v254, s[40:41]
	s_add_u32 m0, m0, 0x1000
	s_nop 0
	global_load_lds_dwordx4 v254, s[42:43]
	s_add_u32 m0, m0, 0x1000
	s_nop 0
	global_load_lds_dwordx4 v254, s[44:45]
	v_add_u32_e32 v254, 0x80, v254
	s_add_u32 m0, s46, 0x8000
	s_nop 0
	global_load_lds_dwordx4 v254, s[28:29]
	s_add_u32 m0, m0, 0x1000
	s_nop 0
	global_load_lds_dwordx4 v254, s[30:31]
	s_add_u32 m0, m0, 0x1000
	s_nop 0
	global_load_lds_dwordx4 v254, s[34:35]
	s_add_u32 m0, m0, 0x1000
	s_nop 0
	global_load_lds_dwordx4 v254, s[36:37]
	s_add_u32 m0, m0, 0x1000
	s_nop 0
	global_load_lds_dwordx4 v254, s[38:39]
	s_add_u32 m0, m0, 0x1000
	s_nop 0
	global_load_lds_dwordx4 v254, s[40:41]
	s_add_u32 m0, m0, 0x1000
	s_nop 0
	global_load_lds_dwordx4 v254, s[42:43]
	s_add_u32 m0, m0, 0x1000
	s_nop 0
	global_load_lds_dwordx4 v254, s[44:45]
	v_add_u32_e32 v254, 0x80, v254

.Lgk_loop_p14:
	s_waitcnt vmcnt(8)
	s_barrier
	ds_read_b128 v[64:67], v255
	ds_read_b128 v[76:79], v157 offset:16384
	ds_read_b128 v[80:83], v157 offset:20480
	ds_read_b128 v[84:87], v157 offset:24576
	ds_read_b128 v[88:91], v157 offset:28672
	ds_read_b128 v[92:95], v162
	ds_read_b128 v[96:99], v163 offset:16384
	ds_read_b128 v[100:103], v163 offset:20480
	ds_read_b128 v[118:121], v163 offset:24576
	ds_read_b128 v[122:125], v163 offset:28672
	ds_read_b128 v[172:175], v164
	ds_read_b128 v[226:229], v165 offset:16384
	ds_read_b128 v[230:233], v165 offset:20480
	ds_read_b128 v[234:237], v165 offset:24576
	ds_read_b128 v[238:241], v165 offset:28672
	ds_read_b128 v[242:245], v167
	ds_read_b128 v[246:249], v168 offset:16384
	ds_read_b128 v[250:253], v168 offset:20480
	ds_read_b128 v[112:115], v168 offset:24576
	ds_read_b128 v[158:161], v168 offset:28672
	s_waitcnt lgkmcnt(0)
	s_barrier
	s_mov_b32 m0, s46
	s_setprio 1
	v_mfma_f32_32x32x16_bf16 v[48:63], v[64:67], v[76:79], v[48:63]
	v_mfma_f32_32x32x16_bf16 v[32:47], v[64:67], v[80:83], v[32:47]
	global_load_lds_dwordx4 v254, s[28:29]
	s_add_u32 m0, m0, 0x1000
	v_mfma_f32_32x32x16_bf16 v[16:31], v[64:67], v[84:87], v[16:31]
	v_mfma_f32_32x32x16_bf16 v[0:15], v[64:67], v[88:91], v[0:15]
	global_load_lds_dwordx4 v254, s[30:31]
	s_add_u32 m0, m0, 0x1000
	v_mfma_f32_32x32x16_bf16 v[48:63], v[92:95], v[96:99], v[48:63]
	v_mfma_f32_32x32x16_bf16 v[32:47], v[92:95], v[100:103], v[32:47]
	global_load_lds_dwordx4 v254, s[34:35]
	s_add_u32 m0, m0, 0x1000
	v_mfma_f32_32x32x16_bf16 v[16:31], v[92:95], v[118:121], v[16:31]
	v_mfma_f32_32x32x16_bf16 v[0:15], v[92:95], v[122:125], v[0:15]
	global_load_lds_dwordx4 v254, s[36:37]
	s_add_u32 m0, m0, 0x1000
	v_mfma_f32_32x32x16_bf16 v[48:63], v[172:175], v[226:229], v[48:63]
	v_mfma_f32_32x32x16_bf16 v[32:47], v[172:175], v[230:233], v[32:47]
	global_load_lds_dwordx4 v254, s[38:39]
	s_add_u32 m0, m0, 0x1000
	v_mfma_f32_32x32x16_bf16 v[16:31], v[172:175], v[234:237], v[16:31]
	v_mfma_f32_32x32x16_bf16 v[0:15], v[172:175], v[238:241], v[0:15]
	global_load_lds_dwordx4 v254, s[40:41]
	s_add_u32 m0, m0, 0x1000
	v_mfma_f32_32x32x16_bf16 v[48:63], v[242:245], v[246:249], v[48:63]
	v_mfma_f32_32x32x16_bf16 v[32:47], v[242:245], v[250:253], v[32:47]
	global_load_lds_dwordx4 v254, s[42:43]
	s_add_u32 m0, m0, 0x1000
	v_mfma_f32_32x32x16_bf16 v[16:31], v[242:245], v[112:115], v[16:31]
	v_mfma_f32_32x32x16_bf16 v[0:15], v[242:245], v[158:161], v[0:15]
	global_load_lds_dwordx4 v254, s[44:45]
	s_setprio 0
	v_add_u32_e32 v254, 0x80, v254
	s_waitcnt vmcnt(8)
	s_barrier
	ds_read_b128 v[64:67], v255 offset:32768
	ds_read_b128 v[76:79], v157 offset:49152
	ds_read_b128 v[80:83], v157 offset:53248
	ds_read_b128 v[84:87], v157 offset:57344
	ds_read_b128 v[88:91], v157 offset:61440
	ds_read_b128 v[92:95], v162 offset:32768
	ds_read_b128 v[96:99], v163 offset:49152
	ds_read_b128 v[100:103], v163 offset:53248
	ds_read_b128 v[118:121], v163 offset:57344
	ds_read_b128 v[122:125], v163 offset:61440
	ds_read_b128 v[172:175], v164 offset:32768
	ds_read_b128 v[226:229], v165 offset:49152
	ds_read_b128 v[230:233], v165 offset:53248
	ds_read_b128 v[234:237], v165 offset:57344
	ds_read_b128 v[238:241], v165 offset:61440
	ds_read_b128 v[242:245], v167 offset:32768
	ds_read_b128 v[246:249], v168 offset:49152
	ds_read_b128 v[250:253], v168 offset:53248
	ds_read_b128 v[112:115], v168 offset:57344
	ds_read_b128 v[158:161], v168 offset:61440
	s_waitcnt lgkmcnt(0)
	s_barrier
	s_add_u32 m0, s46, 0x8000
	s_setprio 1
	v_mfma_f32_32x32x16_bf16 v[48:63], v[64:67], v[76:79], v[48:63]
	v_mfma_f32_32x32x16_bf16 v[32:47], v[64:67], v[80:83], v[32:47]
	global_load_lds_dwordx4 v254, s[28:29]
	s_add_u32 m0, m0, 0x1000
	v_mfma_f32_32x32x16_bf16 v[16:31], v[64:67], v[84:87], v[16:31]
	v_mfma_f32_32x32x16_bf16 v[0:15], v[64:67], v[88:91], v[0:15]
	global_load_lds_dwordx4 v254, s[30:31]
	s_add_u32 m0, m0, 0x1000
	v_mfma_f32_32x32x16_bf16 v[48:63], v[92:95], v[96:99], v[48:63]
	v_mfma_f32_32x32x16_bf16 v[32:47], v[92:95], v[100:103], v[32:47]
	global_load_lds_dwordx4 v254, s[34:35]
	s_add_u32 m0, m0, 0x1000
	v_mfma_f32_32x32x16_bf16 v[16:31], v[92:95], v[118:121], v[16:31]
	v_mfma_f32_32x32x16_bf16 v[0:15], v[92:95], v[122:125], v[0:15]
	global_load_lds_dwordx4 v254, s[36:37]
	s_add_u32 m0, m0, 0x1000
	v_mfma_f32_32x32x16_bf16 v[48:63], v[172:175], v[226:229], v[48:63]
	v_mfma_f32_32x32x16_bf16 v[32:47], v[172:175], v[230:233], v[32:47]
	global_load_lds_dwordx4 v254, s[38:39]
	s_add_u32 m0, m0, 0x1000
	v_mfma_f32_32x32x16_bf16 v[16:31], v[172:175], v[234:237], v[16:31]
	v_mfma_f32_32x32x16_bf16 v[0:15], v[172:175], v[238:241], v[0:15]
	global_load_lds_dwordx4 v254, s[40:41]
	s_add_u32 m0, m0, 0x1000
	v_mfma_f32_32x32x16_bf16 v[48:63], v[242:245], v[246:249], v[48:63]
	v_mfma_f32_32x32x16_bf16 v[32:47], v[242:245], v[250:253], v[32:47]
	global_load_lds_dwordx4 v254, s[42:43]
	s_add_u32 m0, m0, 0x1000
	v_mfma_f32_32x32x16_bf16 v[16:31], v[242:245], v[112:115], v[16:31]
	v_mfma_f32_32x32x16_bf16 v[0:15], v[242:245], v[158:161], v[0:15]
	global_load_lds_dwordx4 v254, s[44:45]
	s_setprio 0
	v_add_u32_e32 v254, 0x80, v254
	s_sub_u32 s47, s47, 1
	s_cmp_lg_u32 s47, 0
	s_cbranch_scc1 .Lgk_loop_p14
	s_add_u32 s50, s3, s33
	s_cmp_gt_u32 s50, 0x5ff
	s_cbranch_scc1 .Lgk_tailplain_p14
.LBB0_1171_pf_p14:
	s_mul_hi_i32 s52, s50, 0x2aaaaaab
	s_lshr_b32 s53, s52, 31
	s_ashr_i32 s52, s52, 4
	s_add_i32 s52, s52, s53
	s_mul_i32 s61, s52, 0xffffffa0
	s_add_i32 s61, s61, s50
	s_lshl_b32 s53, s52, 3
	s_ashr_i32 s52, s61, 31
	s_lshr_b32 s52, s52, 29
	s_add_i32 s52, s61, s52
	s_ashr_i32 s60, s52, 3
	s_and_b32 s52, s52, -8
	s_sub_i32 s51, s61, s52
	s_add_i32 s51, s51, s53
	s_lshl_b32 s56, s51, 7
	s_lshl_b32 s54, s60, 7
	s_ashr_i32 s57, s56, 31
	s_ashr_i32 s55, s54, 31
	s_lshl_b64 s[52:53], s[56:57], 11
	s_lshl_b64 s[58:59], s[54:55], 11
	s_lshl_b32 s48, s56, 11
	s_add_u32 s28, s14, s48
	s_addc_u32 s29, s15, 0
	s_add_u32 s28, s28, 0x679f000
	s_addc_u32 s29, s29, 0
	s_add_u32 s30, s28, 0x10000
	s_addc_u32 s31, s29, 0
	s_add_u32 s34, s30, 0x10000
	s_addc_u32 s35, s31, 0
	s_add_u32 s36, s34, 0x10000
	s_addc_u32 s37, s35, 0
	s_lshl_b32 s48, s54, 11
	s_add_u32 s38, s14, s48
	s_addc_u32 s39, s15, 0
	s_add_u32 s38, s38, 0xda0000
	s_addc_u32 s39, s39, 0
	s_add_u32 s40, s38, 0x10000
	s_addc_u32 s41, s39, 0
	s_add_u32 s42, s40, 0x10000
	s_addc_u32 s43, s41, 0
	s_add_u32 s44, s42, 0x10000
	s_addc_u32 s45, s43, 0
	v_mov_b32_e32 v254, v110
	s_mov_b32 s49, 1
	s_waitcnt vmcnt(8)
	s_barrier
	ds_read_b128 v[64:67], v255
	ds_read_b128 v[76:79], v157 offset:16384
	ds_read_b128 v[80:83], v157 offset:20480
	ds_read_b128 v[84:87], v157 offset:24576
	ds_read_b128 v[88:91], v157 offset:28672
	ds_read_b128 v[92:95], v162
	ds_read_b128 v[96:99], v163 offset:16384
	ds_read_b128 v[100:103], v163 offset:20480
	ds_read_b128 v[118:121], v163 offset:24576
	ds_read_b128 v[122:125], v163 offset:28672
	ds_read_b128 v[172:175], v164
	ds_read_b128 v[226:229], v165 offset:16384
	ds_read_b128 v[230:233], v165 offset:20480
	ds_read_b128 v[234:237], v165 offset:24576
	ds_read_b128 v[238:241], v165 offset:28672
	ds_read_b128 v[242:245], v167
	ds_read_b128 v[246:249], v168 offset:16384
	ds_read_b128 v[250:253], v168 offset:20480
	ds_read_b128 v[112:115], v168 offset:24576
	ds_read_b128 v[158:161], v168 offset:28672
	s_waitcnt lgkmcnt(0)
	s_barrier
	s_mov_b32 m0, s46
	s_setprio 1
	v_mfma_f32_32x32x16_bf16 v[48:63], v[64:67], v[76:79], v[48:63]
	v_mfma_f32_32x32x16_bf16 v[32:47], v[64:67], v[80:83], v[32:47]
	global_load_lds_dwordx4 v254, s[28:29]
	s_add_u32 m0, m0, 0x1000
	v_mfma_f32_32x32x16_bf16 v[16:31], v[64:67], v[84:87], v[16:31]
	v_mfma_f32_32x32x16_bf16 v[0:15], v[64:67], v[88:91], v[0:15]
	global_load_lds_dwordx4 v254, s[30:31]
	s_add_u32 m0, m0, 0x1000
	v_mfma_f32_32x32x16_bf16 v[48:63], v[92:95], v[96:99], v[48:63]
	v_mfma_f32_32x32x16_bf16 v[32:47], v[92:95], v[100:103], v[32:47]
	global_load_lds_dwordx4 v254, s[34:35]
	s_add_u32 m0, m0, 0x1000
	v_mfma_f32_32x32x16_bf16 v[16:31], v[92:95], v[118:121], v[16:31]
	v_mfma_f32_32x32x16_bf16 v[0:15], v[92:95], v[122:125], v[0:15]
	global_load_lds_dwordx4 v254, s[36:37]
	s_add_u32 m0, m0, 0x1000
	v_mfma_f32_32x32x16_bf16 v[48:63], v[172:175], v[226:229], v[48:63]
	v_mfma_f32_32x32x16_bf16 v[32:47], v[172:175], v[230:233], v[32:47]
	global_load_lds_dwordx4 v254, s[38:39]
	s_add_u32 m0, m0, 0x1000
	v_mfma_f32_32x32x16_bf16 v[16:31], v[172:175], v[234:237], v[16:31]
	v_mfma_f32_32x32x16_bf16 v[0:15], v[172:175], v[238:241], v[0:15]
	global_load_lds_dwordx4 v254, s[40:41]
	s_add_u32 m0, m0, 0x1000
	v_mfma_f32_32x32x16_bf16 v[48:63], v[242:245], v[246:249], v[48:63]
	v_mfma_f32_32x32x16_bf16 v[32:47], v[242:245], v[250:253], v[32:47]
	global_load_lds_dwordx4 v254, s[42:43]
	s_add_u32 m0, m0, 0x1000
	v_mfma_f32_32x32x16_bf16 v[16:31], v[242:245], v[112:115], v[16:31]
	v_mfma_f32_32x32x16_bf16 v[0:15], v[242:245], v[158:161], v[0:15]
	global_load_lds_dwordx4 v254, s[44:45]
	s_setprio 0
	v_add_u32_e32 v254, 0x80, v254
	s_waitcnt vmcnt(8)
	s_barrier
	ds_read_b128 v[64:67], v255 offset:32768
	ds_read_b128 v[76:79], v157 offset:49152
	ds_read_b128 v[80:83], v157 offset:53248
	ds_read_b128 v[84:87], v157 offset:57344
	ds_read_b128 v[88:91], v157 offset:61440
	ds_read_b128 v[92:95], v162 offset:32768
	ds_read_b128 v[96:99], v163 offset:49152
	ds_read_b128 v[100:103], v163 offset:53248
	ds_read_b128 v[118:121], v163 offset:57344
	ds_read_b128 v[122:125], v163 offset:61440
	ds_read_b128 v[172:175], v164 offset:32768
	ds_read_b128 v[226:229], v165 offset:49152
	ds_read_b128 v[230:233], v165 offset:53248
	ds_read_b128 v[234:237], v165 offset:57344
	ds_read_b128 v[238:241], v165 offset:61440
	ds_read_b128 v[242:245], v167 offset:32768
	ds_read_b128 v[246:249], v168 offset:49152
	ds_read_b128 v[250:253], v168 offset:53248
	ds_read_b128 v[112:115], v168 offset:57344
	ds_read_b128 v[158:161], v168 offset:61440
	s_waitcnt lgkmcnt(0)
	s_barrier
	s_add_u32 m0, s46, 0x8000
	s_setprio 1
	v_mfma_f32_32x32x16_bf16 v[48:63], v[64:67], v[76:79], v[48:63]
	v_mfma_f32_32x32x16_bf16 v[32:47], v[64:67], v[80:83], v[32:47]
	global_load_lds_dwordx4 v254, s[28:29]
	s_add_u32 m0, m0, 0x1000
	v_mfma_f32_32x32x16_bf16 v[16:31], v[64:67], v[84:87], v[16:31]
	v_mfma_f32_32x32x16_bf16 v[0:15], v[64:67], v[88:91], v[0:15]
	global_load_lds_dwordx4 v254, s[30:31]
	s_add_u32 m0, m0, 0x1000
	v_mfma_f32_32x32x16_bf16 v[48:63], v[92:95], v[96:99], v[48:63]
	v_mfma_f32_32x32x16_bf16 v[32:47], v[92:95], v[100:103], v[32:47]
	global_load_lds_dwordx4 v254, s[34:35]
	s_add_u32 m0, m0, 0x1000
	v_mfma_f32_32x32x16_bf16 v[16:31], v[92:95], v[118:121], v[16:31]
	v_mfma_f32_32x32x16_bf16 v[0:15], v[92:95], v[122:125], v[0:15]
	global_load_lds_dwordx4 v254, s[36:37]
	s_add_u32 m0, m0, 0x1000
	v_mfma_f32_32x32x16_bf16 v[48:63], v[172:175], v[226:229], v[48:63]
	v_mfma_f32_32x32x16_bf16 v[32:47], v[172:175], v[230:233], v[32:47]
	global_load_lds_dwordx4 v254, s[38:39]
	s_add_u32 m0, m0, 0x1000
	v_mfma_f32_32x32x16_bf16 v[16:31], v[172:175], v[234:237], v[16:31]
	v_mfma_f32_32x32x16_bf16 v[0:15], v[172:175], v[238:241], v[0:15]
	global_load_lds_dwordx4 v254, s[40:41]
	s_add_u32 m0, m0, 0x1000
	v_mfma_f32_32x32x16_bf16 v[48:63], v[242:245], v[246:249], v[48:63]
	v_mfma_f32_32x32x16_bf16 v[32:47], v[242:245], v[250:253], v[32:47]
	global_load_lds_dwordx4 v254, s[42:43]
	s_add_u32 m0, m0, 0x1000
	v_mfma_f32_32x32x16_bf16 v[16:31], v[242:245], v[112:115], v[16:31]
	v_mfma_f32_32x32x16_bf16 v[0:15], v[242:245], v[158:161], v[0:15]
	global_load_lds_dwordx4 v254, s[44:45]
	s_setprio 0
	v_add_u32_e32 v254, 0x80, v254
	s_branch .LBB0_1175
.Lgk_tailplain_p14:
	s_mov_b32 s49, 0
	s_waitcnt vmcnt(8)
	s_barrier
	ds_read_b128 v[64:67], v255
	ds_read_b128 v[76:79], v157 offset:16384
	ds_read_b128 v[80:83], v157 offset:20480
	ds_read_b128 v[84:87], v157 offset:24576
	ds_read_b128 v[88:91], v157 offset:28672
	ds_read_b128 v[92:95], v162
	ds_read_b128 v[96:99], v163 offset:16384
	ds_read_b128 v[100:103], v163 offset:20480
	ds_read_b128 v[118:121], v163 offset:24576
	ds_read_b128 v[122:125], v163 offset:28672
	ds_read_b128 v[172:175], v164
	ds_read_b128 v[226:229], v165 offset:16384
	ds_read_b128 v[230:233], v165 offset:20480
	ds_read_b128 v[234:237], v165 offset:24576
	ds_read_b128 v[238:241], v165 offset:28672
	ds_read_b128 v[242:245], v167
	ds_read_b128 v[246:249], v168 offset:16384
	ds_read_b128 v[250:253], v168 offset:20480
	ds_read_b128 v[112:115], v168 offset:24576
	ds_read_b128 v[158:161], v168 offset:28672
	s_waitcnt lgkmcnt(0)
	s_barrier
	s_setprio 1
	v_mfma_f32_32x32x16_bf16 v[48:63], v[64:67], v[76:79], v[48:63]
	v_mfma_f32_32x32x16_bf16 v[32:47], v[64:67], v[80:83], v[32:47]
	v_mfma_f32_32x32x16_bf16 v[16:31], v[64:67], v[84:87], v[16:31]
	v_mfma_f32_32x32x16_bf16 v[0:15], v[64:67], v[88:91], v[0:15]
	v_mfma_f32_32x32x16_bf16 v[48:63], v[92:95], v[96:99], v[48:63]
	v_mfma_f32_32x32x16_bf16 v[32:47], v[92:95], v[100:103], v[32:47]
	v_mfma_f32_32x32x16_bf16 v[16:31], v[92:95], v[118:121], v[16:31]
	v_mfma_f32_32x32x16_bf16 v[0:15], v[92:95], v[122:125], v[0:15]
	v_mfma_f32_32x32x16_bf16 v[48:63], v[172:175], v[226:229], v[48:63]
	v_mfma_f32_32x32x16_bf16 v[32:47], v[172:175], v[230:233], v[32:47]
	v_mfma_f32_32x32x16_bf16 v[16:31], v[172:175], v[234:237], v[16:31]
	v_mfma_f32_32x32x16_bf16 v[0:15], v[172:175], v[238:241], v[0:15]
	v_mfma_f32_32x32x16_bf16 v[48:63], v[242:245], v[246:249], v[48:63]
	v_mfma_f32_32x32x16_bf16 v[32:47], v[242:245], v[250:253], v[32:47]
	v_mfma_f32_32x32x16_bf16 v[16:31], v[242:245], v[112:115], v[16:31]
	v_mfma_f32_32x32x16_bf16 v[0:15], v[242:245], v[158:161], v[0:15]
	s_setprio 0
	s_waitcnt vmcnt(0)
	s_barrier
	ds_read_b128 v[64:67], v255 offset:32768
	ds_read_b128 v[76:79], v157 offset:49152
	ds_read_b128 v[80:83], v157 offset:53248
	ds_read_b128 v[84:87], v157 offset:57344
	ds_read_b128 v[88:91], v157 offset:61440
	ds_read_b128 v[92:95], v162 offset:32768
	ds_read_b128 v[96:99], v163 offset:49152
	ds_read_b128 v[100:103], v163 offset:53248
	ds_read_b128 v[118:121], v163 offset:57344
	ds_read_b128 v[122:125], v163 offset:61440
	ds_read_b128 v[172:175], v164 offset:32768
	ds_read_b128 v[226:229], v165 offset:49152
	ds_read_b128 v[230:233], v165 offset:53248
	ds_read_b128 v[234:237], v165 offset:57344
	ds_read_b128 v[238:241], v165 offset:61440
	ds_read_b128 v[242:245], v167 offset:32768
	ds_read_b128 v[246:249], v168 offset:49152
	ds_read_b128 v[250:253], v168 offset:53248
	ds_read_b128 v[112:115], v168 offset:57344
	ds_read_b128 v[158:161], v168 offset:61440
	s_waitcnt lgkmcnt(0)
	s_barrier
	s_setprio 1
	v_mfma_f32_32x32x16_bf16 v[48:63], v[64:67], v[76:79], v[48:63]
	v_mfma_f32_32x32x16_bf16 v[32:47], v[64:67], v[80:83], v[32:47]
	v_mfma_f32_32x32x16_bf16 v[16:31], v[64:67], v[84:87], v[16:31]
	v_mfma_f32_32x32x16_bf16 v[0:15], v[64:67], v[88:91], v[0:15]
	v_mfma_f32_32x32x16_bf16 v[48:63], v[92:95], v[96:99], v[48:63]
	v_mfma_f32_32x32x16_bf16 v[32:47], v[92:95], v[100:103], v[32:47]
	v_mfma_f32_32x32x16_bf16 v[16:31], v[92:95], v[118:121], v[16:31]
	v_mfma_f32_32x32x16_bf16 v[0:15], v[92:95], v[122:125], v[0:15]
	v_mfma_f32_32x32x16_bf16 v[48:63], v[172:175], v[226:229], v[48:63]
	v_mfma_f32_32x32x16_bf16 v[32:47], v[172:175], v[230:233], v[32:47]
	v_mfma_f32_32x32x16_bf16 v[16:31], v[172:175], v[234:237], v[16:31]
	v_mfma_f32_32x32x16_bf16 v[0:15], v[172:175], v[238:241], v[0:15]
	v_mfma_f32_32x32x16_bf16 v[48:63], v[242:245], v[246:249], v[48:63]
	v_mfma_f32_32x32x16_bf16 v[32:47], v[242:245], v[250:253], v[32:47]
	v_mfma_f32_32x32x16_bf16 v[16:31], v[242:245], v[112:115], v[16:31]
	v_mfma_f32_32x32x16_bf16 v[0:15], v[242:245], v[158:161], v[0:15]
	s_setprio 0
	s_branch .LBB0_1175

.LBB0_1179:
	v_add_u32_e32 v118, s66, v133
	v_ashrrev_i32_e32 v119, 31, v118
	v_lshl_add_u64 v[64:65], v[118:119], 2, s[18:19]
	v_add_co_u32_e32 v66, vcc, 0x10000, v64
	v_or_b32_e32 v120, 8, v118
	s_nop 0
	v_addc_co_u32_e32 v67, vcc, 0, v65, vcc
	global_load_dwordx4 v[92:95], v[64:65], off
	global_load_dwordx4 v[96:99], v[66:67], off
	v_add_co_u32_e32 v66, vcc, 0x20000, v64
	v_ashrrev_i32_e32 v121, 31, v120
	s_nop 0
	v_addc_co_u32_e32 v67, vcc, 0, v65, vcc
	v_add_co_u32_e32 v68, vcc, 0x30000, v64
	v_lshl_add_u64 v[88:89], v[120:121], 2, s[18:19]
	s_nop 0
	v_addc_co_u32_e32 v69, vcc, 0, v65, vcc
	global_load_dwordx4 v[100:103], v[66:67], off
	global_load_dwordx4 v[124:127], v[68:69], off
	v_add_co_u32_e32 v66, vcc, 0x40000, v64
	v_or_b32_e32 v122, 9, v118
	s_nop 0
	v_addc_co_u32_e32 v67, vcc, 0, v65, vcc
	v_add_co_u32_e32 v68, vcc, 0x50000, v64
	v_ashrrev_i32_e32 v123, 31, v122
	s_nop 0
	v_addc_co_u32_e32 v69, vcc, 0, v65, vcc
	global_load_dwordx4 v[172:175], v[66:67], off
	global_load_dwordx4 v[176:179], v[68:69], off
	v_add_co_u32_e32 v66, vcc, 0x60000, v64
	v_lshl_add_u64 v[104:105], v[122:123], 2, s[18:19]
	s_nop 0
	v_addc_co_u32_e32 v67, vcc, 0, v65, vcc
	v_add_co_u32_e32 v64, vcc, 0x70000, v64
	global_load_dwordx4 v[180:183], v[66:67], off
	s_nop 0
	v_addc_co_u32_e32 v65, vcc, 0, v65, vcc
	global_load_dwordx4 v[184:187], v[64:65], off
	v_add_co_u32_e32 v64, vcc, s75, v88
	s_lshl_b64 s[70:71], s[70:71], 2
	s_nop 0
	v_addc_co_u32_e32 v65, vcc, 0, v89, vcc
	v_add_co_u32_e32 v68, vcc, s76, v88
	global_load_dword v188, v[88:89], off
	s_nop 0
	global_load_dwordx4 v[64:67], v[64:65], off
	v_addc_co_u32_e32 v69, vcc, 0, v89, vcc
	v_add_co_u32_e32 v72, vcc, s77, v88
	s_add_u32 s70, s10, s70
	s_nop 0
	v_addc_co_u32_e32 v73, vcc, 0, v89, vcc
	v_add_co_u32_e32 v76, vcc, s78, v88
	global_load_dwordx4 v[68:71], v[68:69], off
	s_nop 0
	global_load_dwordx4 v[72:75], v[72:73], off
	v_addc_co_u32_e32 v77, vcc, 0, v89, vcc
	v_add_co_u32_e32 v80, vcc, s79, v88
	s_addc_u32 s71, s11, s71
	s_nop 0
	v_addc_co_u32_e32 v81, vcc, 0, v89, vcc
	v_add_co_u32_e32 v84, vcc, s80, v88
	global_load_dwordx4 v[76:79], v[76:77], off
	s_nop 0
	global_load_dwordx4 v[80:83], v[80:81], off
	v_addc_co_u32_e32 v85, vcc, 0, v89, vcc
	v_add_co_u32_e32 v88, vcc, s81, v88
	global_load_dwordx4 v[84:87], v[84:85], off
	s_nop 0
	v_addc_co_u32_e32 v89, vcc, 0, v89, vcc
	global_load_dwordx4 v[88:91], v[88:89], off
	s_cmpk_gt_i32 s85, 0x4f
	global_load_dwordx3 v[104:106], v[104:105], off
	s_waitcnt vmcnt(0)
	v_mov_b32_e32 v190, v92
	v_mov_b32_e32 v192, v96
	v_mov_b32_e32 v194, v124
	v_or_b32_e32 v124, 16, v118
	v_mov_b32_e32 v191, v172
	v_mov_b32_e32 v193, v176
	v_pk_add_f32 v[190:191], v[190:191], v[192:193]
	v_mov_b32_e32 v172, v93
	v_mov_b32_e32 v176, v97
	v_pk_add_f32 v[92:93], v[172:173], v[176:177]
	v_mov_b32_e32 v192, v100
	v_mov_b32_e32 v100, v126
	v_or_b32_e32 v126, 17, v118
	v_mov_b32_e32 v193, v180
	v_mov_b32_e32 v180, v101
	v_mov_b32_e32 v195, v184
	v_mov_b32_e32 v184, v125
	v_pk_add_f32 v[96:97], v[180:181], v[184:185]
	v_mov_b32_e32 v101, v186
	v_pk_add_f32 v[92:93], v[92:93], v[96:97]
	v_mov_b32_e32 v96, v98
	v_add_f32_e32 v121, v92, v93
	v_mov_b32_e32 v92, v94
	v_mov_b32_e32 v93, v174
	v_mov_b32_e32 v97, v178
	v_pk_add_f32 v[92:93], v[92:93], v[96:97]
	v_mov_b32_e32 v96, v102
	v_mov_b32_e32 v97, v182
	v_pk_add_f32 v[96:97], v[96:97], v[100:101]
	v_mov_b32_e32 v174, v95
	v_pk_add_f32 v[92:93], v[92:93], v[96:97]
	v_mov_b32_e32 v178, v99
	v_mov_b32_e32 v182, v103
	v_mov_b32_e32 v186, v127
	v_add_f32_e32 v123, v92, v93
	v_pk_add_f32 v[92:93], v[174:175], v[178:179]
	v_pk_add_f32 v[94:95], v[182:183], v[186:187]
	v_ashrrev_i32_e32 v125, 31, v124
	v_pk_add_f32 v[92:93], v[92:93], v[94:95]
	v_lshl_add_u64 v[100:101], v[124:125], 2, s[18:19]
	v_add_f32_e32 v171, v92, v93
	v_mov_b32_e32 v92, v64
	v_mov_b32_e32 v189, v76
	v_mov_b32_e32 v93, v80
	v_mov_b32_e32 v94, v68
	v_mov_b32_e32 v96, v72
	global_load_dword v64, v[100:101], off
	v_mov_b32_e32 v80, v65
	v_mov_b32_e32 v95, v84
	v_pk_add_f32 v[92:93], v[188:189], v[92:93]
	v_ashrrev_i32_e32 v127, 31, v126
	v_mov_b32_e32 v97, v88
	v_pk_add_f32 v[94:95], v[94:95], v[96:97]
	v_mov_b32_e32 v76, v104
	v_pk_add_f32 v[76:77], v[76:77], v[80:81]
	v_add_co_u32_e32 v80, vcc, s75, v100
	v_pk_add_f32 v[92:93], v[92:93], v[94:95]
	s_nop 0
	v_addc_co_u32_e32 v81, vcc, 0, v101, vcc
	v_add_f32_e32 v225, v92, v93
	v_add_co_u32_e32 v92, vcc, s76, v100
	v_mov_b32_e32 v84, v69
	s_nop 0
	v_addc_co_u32_e32 v93, vcc, 0, v101, vcc
	global_load_dwordx4 v[172:175], v[80:81], off
	global_load_dwordx4 v[176:179], v[92:93], off
	v_add_co_u32_e32 v80, vcc, s77, v100
	v_mov_b32_e32 v88, v73
	s_nop 0
	v_addc_co_u32_e32 v81, vcc, 0, v101, vcc
	v_add_co_u32_e32 v96, vcc, s78, v100
	v_pk_add_f32 v[68:69], v[84:85], v[88:89]
	s_nop 0
	v_addc_co_u32_e32 v97, vcc, 0, v101, vcc
	global_load_dwordx4 v[92:95], v[80:81], off
	global_load_dwordx4 v[180:183], v[96:97], off
	v_add_co_u32_e32 v80, vcc, s79, v100
	v_or_b32_e32 v84, 24, v118
	s_nop 0
	v_addc_co_u32_e32 v81, vcc, 0, v101, vcc
	v_add_co_u32_e32 v96, vcc, s80, v100
	v_ashrrev_i32_e32 v85, 31, v84
	s_nop 0
	v_addc_co_u32_e32 v97, vcc, 0, v101, vcc
	global_load_dwordx4 v[184:187], v[80:81], off
	s_nop 0
	global_load_dwordx4 v[96:99], v[96:97], off
	v_add_co_u32_e32 v80, vcc, s81, v100
	v_lshl_add_u64 v[72:73], v[84:85], 2, s[18:19]
	s_nop 0
	v_addc_co_u32_e32 v81, vcc, 0, v101, vcc
	global_load_dwordx4 v[100:103], v[80:81], off
	v_lshl_add_u64 v[80:81], v[126:127], 2, s[18:19]
	global_load_dwordx3 v[196:198], v[80:81], off
	v_pk_add_f32 v[192:193], v[192:193], v[194:195]
	v_pk_add_f32 v[68:69], v[76:77], v[68:69]
	v_add_co_u32_e32 v76, vcc, s75, v72
	v_pk_add_f32 v[190:191], v[190:191], v[192:193]
	s_nop 0
	v_addc_co_u32_e32 v77, vcc, 0, v73, vcc
	v_add_f32_e32 v119, v190, v191
	global_load_dword v80, v[72:73], off
	global_load_dwordx4 v[188:191], v[76:77], off
	v_add_co_u32_e32 v76, vcc, s76, v72
	v_or_b32_e32 v104, 25, v118
	s_nop 0
	v_addc_co_u32_e32 v77, vcc, 0, v73, vcc
	v_add_co_u32_e32 v88, vcc, s77, v72
	v_add_f32_e32 v125, v68, v69
	s_nop 0
	v_addc_co_u32_e32 v89, vcc, 0, v73, vcc
	global_load_dwordx4 v[192:195], v[76:77], off
	global_load_dwordx4 v[202:205], v[88:89], off
	v_add_co_u32_e32 v76, vcc, s78, v72
	v_mov_b32_e32 v68, v105
	s_nop 0
	v_addc_co_u32_e32 v77, vcc, 0, v73, vcc
	v_add_co_u32_e32 v88, vcc, s79, v72
	v_ashrrev_i32_e32 v105, 31, v104
	s_nop 0
	v_addc_co_u32_e32 v89, vcc, 0, v73, vcc
	global_load_dwordx4 v[206:209], v[76:77], off
	global_load_dwordx4 v[210:213], v[88:89], off
	v_add_co_u32_e32 v76, vcc, s80, v72
	v_mov_b32_e32 v69, v78
	s_nop 0
	v_addc_co_u32_e32 v77, vcc, 0, v73, vcc
	v_add_co_u32_e32 v72, vcc, s81, v72
	global_load_dwordx4 v[214:217], v[76:77], off
	s_nop 0
	v_addc_co_u32_e32 v73, vcc, 0, v73, vcc
	global_load_dwordx4 v[218:221], v[72:73], off
	v_lshl_add_u64 v[72:73], v[104:105], 2, s[18:19]
	global_load_dwordx3 v[222:224], v[72:73], off
	v_mov_b32_e32 v72, v66
	v_mov_b32_e32 v73, v82
	v_pk_add_f32 v[68:69], v[68:69], v[72:73]
	v_mov_b32_e32 v72, v70
	v_mov_b32_e32 v73, v86
	v_mov_b32_e32 v76, v74
	v_mov_b32_e32 v77, v90
	v_pk_add_f32 v[72:73], v[72:73], v[76:77]
	v_mov_b32_e32 v78, v106
	v_pk_add_f32 v[68:69], v[68:69], v[72:73]
	v_mov_b32_e32 v82, v67
	v_mov_b32_e32 v86, v71
	v_mov_b32_e32 v90, v75
	v_add_f32_e32 v72, v68, v69
	v_pk_add_f32 v[66:67], v[78:79], v[82:83]
	v_pk_add_f32 v[68:69], v[86:87], v[90:91]
	s_waitcnt vmcnt(13)
	v_mov_b32_e32 v65, v180
	v_pk_add_f32 v[66:67], v[66:67], v[68:69]
	v_mov_b32_e32 v68, v92
	v_add_f32_e32 v71, v66, v67
	v_mov_b32_e32 v66, v172
	s_waitcnt vmcnt(12)
	v_mov_b32_e32 v67, v184
	v_pk_add_f32 v[64:65], v[64:65], v[66:67]
	v_mov_b32_e32 v66, v176
	s_waitcnt vmcnt(11)
	v_mov_b32_e32 v67, v96
	v_mov_b32_e32 v184, v173
	v_mov_b32_e32 v96, v177
	s_waitcnt vmcnt(10)
	v_mov_b32_e32 v69, v100
	v_pk_add_f32 v[66:67], v[66:67], v[68:69]
	s_waitcnt vmcnt(9)
	v_mov_b32_e32 v180, v196
	v_pk_add_f32 v[64:65], v[64:65], v[66:67]
	v_mov_b32_e32 v100, v93
	v_add_f32_e32 v73, v64, v65
	v_pk_add_f32 v[64:65], v[180:181], v[184:185]
	v_pk_add_f32 v[66:67], v[96:97], v[100:101]
	v_mov_b32_e32 v68, v94
	v_pk_add_f32 v[64:65], v[64:65], v[66:67]
	v_mov_b32_e32 v66, v174
	v_add_f32_e32 v75, v64, v65
	v_mov_b32_e32 v64, v197
	v_mov_b32_e32 v65, v182
	v_mov_b32_e32 v67, v186
	v_pk_add_f32 v[64:65], v[64:65], v[66:67]
	v_mov_b32_e32 v66, v178
	v_mov_b32_e32 v67, v98
	v_mov_b32_e32 v69, v102
	v_pk_add_f32 v[66:67], v[66:67], v[68:69]
	v_mov_b32_e32 v102, v95
	v_pk_add_f32 v[64:65], v[64:65], v[66:67]
	v_or_b32_e32 v66, s4, v108
	v_ashrrev_i32_e32 v67, 31, v66
	v_lshl_add_u64 v[66:67], v[66:67], 2, s[70:71]
	global_load_dword v97, v[66:67], off
	global_load_dword v96, v[66:67], off offset:128
	global_load_dword v95, v[66:67], off offset:256
	global_load_dword v94, v[66:67], off offset:384
	v_mov_b32_e32 v182, v198
	v_mov_b32_e32 v186, v175
	v_mov_b32_e32 v98, v179
	v_add_f32_e32 v76, v64, v65
	v_pk_add_f32 v[64:65], v[182:183], v[186:187]
	v_pk_add_f32 v[66:67], v[98:99], v[102:103]
	s_waitcnt vmcnt(8)
	v_mov_b32_e32 v81, v206
	v_pk_add_f32 v[64:65], v[64:65], v[66:67]
	v_mov_b32_e32 v66, v192
	v_add_f32_e32 v77, v64, v65
	v_mov_b32_e32 v64, v188
	s_waitcnt vmcnt(7)
	v_mov_b32_e32 v65, v210
	v_mov_b32_e32 v68, v202
	v_pk_add_f32 v[64:65], v[80:81], v[64:65]
	s_waitcnt vmcnt(6)
	v_mov_b32_e32 v67, v214
	v_mov_b32_e32 v210, v189
	v_mov_b32_e32 v214, v193
	s_waitcnt vmcnt(5)
	v_mov_b32_e32 v69, v218
	v_pk_add_f32 v[66:67], v[66:67], v[68:69]
	s_waitcnt vmcnt(4)
	v_mov_b32_e32 v206, v222
	v_pk_add_f32 v[64:65], v[64:65], v[66:67]
	v_mov_b32_e32 v218, v203
	v_add_f32_e32 v78, v64, v65
	v_pk_add_f32 v[64:65], v[206:207], v[210:211]
	v_pk_add_f32 v[66:67], v[214:215], v[218:219]
	v_mov_b32_e32 v68, v204
	v_pk_add_f32 v[64:65], v[64:65], v[66:67]
	v_mov_b32_e32 v66, v190
	v_add_f32_e32 v79, v64, v65
	v_mov_b32_e32 v64, v223
	v_mov_b32_e32 v65, v208
	v_mov_b32_e32 v67, v212
	v_pk_add_f32 v[64:65], v[64:65], v[66:67]
	v_mov_b32_e32 v66, v194
	v_mov_b32_e32 v67, v216
	v_mov_b32_e32 v69, v220
	v_pk_add_f32 v[66:67], v[66:67], v[68:69]
	v_mov_b32_e32 v208, v224
	v_pk_add_f32 v[64:65], v[64:65], v[66:67]
	v_mov_b32_e32 v212, v191
	v_mov_b32_e32 v216, v195
	v_mov_b32_e32 v220, v205
	v_add_f32_e32 v69, v64, v65
	v_pk_add_f32 v[64:65], v[208:209], v[212:213]
	v_pk_add_f32 v[66:67], v[216:217], v[220:221]
	s_mov_b64 s[4:5], -1
	v_pk_add_f32 v[64:65], v[64:65], v[66:67]
	v_fmamk_f32 v67, v123, 0x3a800000, v166
	v_rsq_f32_e32 v68, v67
	v_fmamk_f32 v67, v171, 0x3a800000, v166
	v_add_f32_e32 v65, v64, v65
	v_fmamk_f32 v64, v119, 0x3a800000, v166
	v_rsq_f32_e32 v70, v67
	v_fmamk_f32 v67, v225, 0x3a800000, v166
	v_rsq_f32_e32 v64, v64
	v_rsq_f32_e32 v74, v67
	v_fmamk_f32 v67, v125, 0x3a800000, v166
	v_rsq_f32_e32 v98, v67
	v_fmamk_f32 v67, v72, 0x3a800000, v166
	v_rsq_f32_e32 v100, v67
	v_fmamk_f32 v67, v71, 0x3a800000, v166
	v_rsq_f32_e32 v102, v67
	v_fmamk_f32 v67, v73, 0x3a800000, v166
	v_fmamk_f32 v65, v65, 0x3a800000, v166
	v_mov_b32_e32 v72, v32
	v_mov_b32_e32 v73, v48
	v_rsq_f32_e32 v106, v67
	v_fmamk_f32 v67, v75, 0x3a800000, v166
	v_fmamk_f32 v66, v121, 0x3a800000, v166
	v_rsq_f32_e32 v172, v67
	v_fmamk_f32 v67, v76, 0x3a800000, v166
	v_rsq_f32_e32 v66, v66
	v_rsq_f32_e32 v174, v67
	v_fmamk_f32 v67, v77, 0x3a800000, v166
	v_rsq_f32_e32 v176, v67
	v_fmamk_f32 v67, v78, 0x3a800000, v166
	v_rsq_f32_e32 v178, v67
	v_fmamk_f32 v67, v79, 0x3a800000, v166
	s_waitcnt vmcnt(2)
	v_pk_fma_f32 v[90:91], v[72:73], v[64:65], v[96:97] op_sel_hi:[1,0,1]
	v_mov_b32_e32 v72, v0
	v_mov_b32_e32 v73, v16
	v_mov_b32_e32 v16, v1
	v_mov_b32_e32 v0, v34
	v_mov_b32_e32 v1, v50
	v_pk_fma_f32 v[80:81], v[0:1], v[68:69], v[96:97] op_sel_hi:[1,0,1]
	v_mov_b32_e32 v0, v2
	v_mov_b32_e32 v1, v18
	s_waitcnt vmcnt(0)
	v_pk_fma_f32 v[82:83], v[0:1], v[68:69], v[94:95] op_sel_hi:[1,0,1]
	v_mov_b32_e32 v0, v36
	v_mov_b32_e32 v1, v52
	v_pk_fma_f32 v[92:93], v[72:73], v[64:65], v[94:95] op_sel_hi:[1,0,1]
	v_pk_fma_f32 v[72:73], v[0:1], v[74:75], v[96:97] op_sel_hi:[1,0,1]
	v_mov_b32_e32 v0, v4
	v_mov_b32_e32 v1, v20
	v_pk_fma_f32 v[74:75], v[0:1], v[74:75], v[94:95] op_sel_hi:[1,0,1]
	v_mov_b32_e32 v0, v38
	v_mov_b32_e32 v1, v54
	v_rsq_f32_e32 v180, v67
	v_fmamk_f32 v67, v69, 0x3a800000, v166
	v_rsq_f32_e32 v184, v65
	v_mov_b32_e32 v48, v33
	v_pk_fma_f32 v[64:65], v[0:1], v[100:101], v[96:97] op_sel_hi:[1,0,1]
	v_mov_b32_e32 v0, v6
	v_mov_b32_e32 v1, v22
	v_rsq_f32_e32 v182, v67
	v_pk_fma_f32 v[88:89], v[48:49], v[66:67], v[96:97] op_sel_hi:[1,0,1]
	v_pk_fma_f32 v[86:87], v[16:17], v[66:67], v[94:95] op_sel_hi:[1,0,1]
	v_pk_fma_f32 v[66:67], v[0:1], v[100:101], v[94:95] op_sel_hi:[1,0,1]
	v_mov_b32_e32 v0, v40
	v_mov_b32_e32 v1, v56
	v_mov_b32_e32 v54, v39
	v_pk_fma_f32 v[38:39], v[0:1], v[106:107], v[96:97] op_sel_hi:[1,0,1]
	v_mov_b32_e32 v0, v8
	v_mov_b32_e32 v1, v24
	v_pk_fma_f32 v[48:49], v[0:1], v[106:107], v[94:95] op_sel_hi:[1,0,1]
	v_mov_b32_e32 v24, v9
	v_mov_b32_e32 v0, v42
	v_mov_b32_e32 v1, v58
	v_mov_b32_e32 v52, v37
	v_pk_fma_f32 v[36:37], v[24:25], v[172:173], v[94:95] op_sel_hi:[1,0,1]
	v_pk_fma_f32 v[24:25], v[0:1], v[174:175], v[96:97] op_sel_hi:[1,0,1]
	v_mov_b32_e32 v0, v10
	v_mov_b32_e32 v1, v26
	v_pk_fma_f32 v[32:33], v[0:1], v[174:175], v[94:95] op_sel_hi:[1,0,1]
	v_mov_b32_e32 v0, v44
	v_mov_b32_e32 v1, v60
	v_mov_b32_e32 v18, v3
	v_pk_fma_f32 v[16:17], v[0:1], v[178:179], v[96:97] op_sel_hi:[1,0,1]
	v_mov_b32_e32 v0, v12
	v_mov_b32_e32 v1, v28
	v_pk_fma_f32 v[78:79], v[18:19], v[70:71], v[94:95] op_sel_hi:[1,0,1]
	v_pk_fma_f32 v[18:19], v[0:1], v[178:179], v[94:95] op_sel_hi:[1,0,1]
	v_mov_b32_e32 v0, v46
	v_mov_b32_e32 v1, v62
	v_mov_b32_e32 v50, v35
	v_mov_b32_e32 v20, v5
	v_mov_b32_e32 v22, v7
	v_mov_b32_e32 v56, v41
	v_mov_b32_e32 v58, v43
	v_mov_b32_e32 v26, v11
	v_mov_b32_e32 v60, v45
	v_mov_b32_e32 v28, v13
	v_pk_fma_f32 v[4:5], v[0:1], v[182:183], v[96:97] op_sel_hi:[1,0,1]
	v_mov_b32_e32 v0, v14
	v_mov_b32_e32 v1, v30
	v_mov_b32_e32 v62, v47
	v_mov_b32_e32 v30, v15
	v_pk_fma_f32 v[76:77], v[50:51], v[70:71], v[96:97] op_sel_hi:[1,0,1]
	v_pk_fma_f32 v[68:69], v[52:53], v[98:99], v[96:97] op_sel_hi:[1,0,1]
	v_pk_fma_f32 v[70:71], v[20:21], v[98:99], v[94:95] op_sel_hi:[1,0,1]
	v_pk_fma_f32 v[50:51], v[54:55], v[102:103], v[96:97] op_sel_hi:[1,0,1]
	v_pk_fma_f32 v[52:53], v[22:23], v[102:103], v[94:95] op_sel_hi:[1,0,1]
	v_pk_fma_f32 v[34:35], v[56:57], v[172:173], v[96:97] op_sel_hi:[1,0,1]
	v_pk_fma_f32 v[20:21], v[58:59], v[176:177], v[96:97] op_sel_hi:[1,0,1]
	v_pk_fma_f32 v[22:23], v[26:27], v[176:177], v[94:95] op_sel_hi:[1,0,1]
	v_pk_fma_f32 v[8:9], v[60:61], v[180:181], v[96:97] op_sel_hi:[1,0,1]
	v_pk_fma_f32 v[10:11], v[28:29], v[180:181], v[94:95] op_sel_hi:[1,0,1]
	v_pk_fma_f32 v[6:7], v[0:1], v[182:183], v[94:95] op_sel_hi:[1,0,1]
	v_pk_fma_f32 v[0:1], v[62:63], v[184:185], v[96:97] op_sel_hi:[1,0,1]
	v_pk_fma_f32 v[2:3], v[30:31], v[184:185], v[94:95] op_sel_hi:[1,0,1]
	s_cbranch_scc0 .LBB0_1189
	s_add_i32 s8, s84, -10
	s_and_b64 s[4:5], s[0:1], exec
	s_cselect_b32 s4, 0x100, 0
	s_add_i32 s4, s67, s4
	v_add_u32_e32 v31, s4, v133
	s_lshl_b32 s4, s8, 15
	s_lshl_b32 s71, s86, 8
	s_lshl_b32 s8, s8, 7
	s_add_i32 s71, s71, s8
	s_lshl_b32 s70, s86, 16
	v_or_b32_e32 v41, s71, v108
	s_add_i32 s70, s70, s4
	v_mul_lo_u32 v41, v41, s74
	v_or_b32_e32 v40, s70, v134
	v_add_u32_e32 v41, 0x200000, v41
	v_cndmask_b32_e64 v46, v40, v41, s[0:1]
	v_add_u32_e32 v40, v46, v31
	v_ashrrev_i32_e32 v41, 31, v40
	v_cvt_pk_bf16_f32 v42, v91, v89
	v_cvt_pk_bf16_f32 v43, v81, v77
	v_lshl_add_u64 v[40:41], v[40:41], 1, s[20:21]
	global_store_dwordx2 v[40:41], v[42:43], off sc1
	v_or_b32_e32 v40, 8, v31
	v_add_u32_e32 v42, v46, v40
	v_ashrrev_i32_e32 v43, 31, v42
	v_cvt_pk_bf16_f32 v44, v73, v69
	v_cvt_pk_bf16_f32 v45, v65, v51
	v_lshl_add_u64 v[42:43], v[42:43], 1, s[20:21]
	v_or_b32_e32 v41, 16, v31
	global_store_dwordx2 v[42:43], v[44:45], off sc1
	v_add_u32_e32 v42, v46, v41
	v_ashrrev_i32_e32 v43, 31, v42
	v_cvt_pk_bf16_f32 v44, v39, v35
	v_cvt_pk_bf16_f32 v45, v25, v21
	v_lshl_add_u64 v[42:43], v[42:43], 1, s[20:21]
	global_store_dwordx2 v[42:43], v[44:45], off sc1
	v_or_b32_e32 v42, 24, v31
	v_add_u32_e32 v44, v46, v42
	v_ashrrev_i32_e32 v45, 31, v44
	v_cndmask_b32_e64 v43, 0, 1, s[68:69]
	v_or_b32_e32 v30, 1, v118
	v_or_b32_e32 v29, 2, v118
	v_or_b32_e32 v28, 3, v118
	v_or_b32_e32 v27, 10, v118
	v_or_b32_e32 v26, 11, v118
	v_or_b32_e32 v15, 18, v118
	v_or_b32_e32 v14, 19, v118
	v_or_b32_e32 v13, 26, v118
	v_or_b32_e32 v12, 27, v118
	v_cvt_pk_bf16_f32 v46, v17, v9
	v_cvt_pk_bf16_f32 v47, v5, v1
	v_lshl_add_u64 v[44:45], v[44:45], 1, s[20:21]
	v_cmp_ne_u32_e64 s[4:5], 1, v43
	s_andn2_b64 vcc, exec, s[68:69]
	global_store_dwordx2 v[44:45], v[46:47], off sc1
	s_cbranch_vccnz .LBB0_1182
	v_or_b32_e32 v43, s8, v108
	v_lshl_add_u32 v44, v118, 8, v43
	v_ashrrev_i32_e32 v45, 31, v44
	v_lshl_add_u64 v[44:45], v[44:45], 2, s[22:23]
	global_store_dword v[44:45], v91, off sc1
	v_lshl_add_u32 v44, v30, 8, v43
	v_ashrrev_i32_e32 v45, 31, v44
	v_lshl_add_u64 v[44:45], v[44:45], 2, s[22:23]
	global_store_dword v[44:45], v89, off sc1
	v_lshl_add_u32 v44, v29, 8, v43
	v_ashrrev_i32_e32 v45, 31, v44
	v_lshl_add_u64 v[44:45], v[44:45], 2, s[22:23]
	global_store_dword v[44:45], v81, off sc1
	v_lshl_add_u32 v44, v28, 8, v43
	v_ashrrev_i32_e32 v45, 31, v44
	v_lshl_add_u64 v[44:45], v[44:45], 2, s[22:23]
	global_store_dword v[44:45], v77, off sc1
	v_lshl_add_u32 v44, v120, 8, v43
	v_ashrrev_i32_e32 v45, 31, v44
	v_lshl_add_u64 v[44:45], v[44:45], 2, s[22:23]
	global_store_dword v[44:45], v73, off sc1
	v_lshl_add_u32 v44, v122, 8, v43
	v_ashrrev_i32_e32 v45, 31, v44
	v_lshl_add_u64 v[44:45], v[44:45], 2, s[22:23]
	global_store_dword v[44:45], v69, off sc1
	v_lshl_add_u32 v44, v27, 8, v43
	v_ashrrev_i32_e32 v45, 31, v44
	v_lshl_add_u64 v[44:45], v[44:45], 2, s[22:23]
	global_store_dword v[44:45], v65, off sc1
	v_lshl_add_u32 v44, v26, 8, v43
	v_ashrrev_i32_e32 v45, 31, v44
	v_lshl_add_u64 v[44:45], v[44:45], 2, s[22:23]
	global_store_dword v[44:45], v51, off sc1
	v_lshl_add_u32 v44, v124, 8, v43
	v_ashrrev_i32_e32 v45, 31, v44
	v_lshl_add_u64 v[44:45], v[44:45], 2, s[22:23]
	global_store_dword v[44:45], v39, off sc1
	v_lshl_add_u32 v44, v126, 8, v43
	v_ashrrev_i32_e32 v45, 31, v44
	v_lshl_add_u64 v[44:45], v[44:45], 2, s[22:23]
	global_store_dword v[44:45], v35, off sc1
	v_lshl_add_u32 v44, v15, 8, v43
	v_ashrrev_i32_e32 v45, 31, v44
	v_lshl_add_u64 v[44:45], v[44:45], 2, s[22:23]
	global_store_dword v[44:45], v25, off sc1
	v_lshl_add_u32 v44, v14, 8, v43
	v_ashrrev_i32_e32 v45, 31, v44
	v_lshl_add_u64 v[44:45], v[44:45], 2, s[22:23]
	global_store_dword v[44:45], v21, off sc1
	v_lshl_add_u32 v44, v84, 8, v43
	v_ashrrev_i32_e32 v45, 31, v44
	v_lshl_add_u64 v[44:45], v[44:45], 2, s[22:23]
	global_store_dword v[44:45], v17, off sc1
	v_lshl_add_u32 v44, v104, 8, v43
	v_ashrrev_i32_e32 v45, 31, v44
	v_lshl_add_u64 v[44:45], v[44:45], 2, s[22:23]
	global_store_dword v[44:45], v9, off sc1
	v_lshl_add_u32 v44, v13, 8, v43
	v_ashrrev_i32_e32 v45, 31, v44
	v_lshl_add_u64 v[44:45], v[44:45], 2, s[22:23]
	global_store_dword v[44:45], v5, off sc1
	v_lshl_add_u32 v44, v12, 8, v43
	v_ashrrev_i32_e32 v45, 31, v44
	v_lshl_add_u64 v[44:45], v[44:45], 2, s[22:23]
	global_store_dword v[44:45], v1, off sc1
.LBB0_1182:
	v_or_b32_e32 v44, s71, v135
	v_mul_lo_u32 v44, v44, s74
	v_or_b32_e32 v43, s70, v136
	v_add_u32_e32 v44, 0x200000, v44
	v_cndmask_b32_e64 v43, v43, v44, s[0:1]
	v_add_u32_e32 v44, v43, v31
	v_ashrrev_i32_e32 v45, 31, v44
	v_cvt_pk_bf16_f32 v46, v90, v88
	v_cvt_pk_bf16_f32 v47, v80, v76
	v_lshl_add_u64 v[44:45], v[44:45], 1, s[20:21]
	global_store_dwordx2 v[44:45], v[46:47], off sc1
	v_add_u32_e32 v44, v43, v40
	v_ashrrev_i32_e32 v45, 31, v44
	v_cvt_pk_bf16_f32 v46, v72, v68
	v_cvt_pk_bf16_f32 v47, v64, v50
	v_lshl_add_u64 v[44:45], v[44:45], 1, s[20:21]
	global_store_dwordx2 v[44:45], v[46:47], off sc1
	v_add_u32_e32 v44, v43, v41
	v_ashrrev_i32_e32 v45, 31, v44
	v_cvt_pk_bf16_f32 v46, v38, v34
	v_cvt_pk_bf16_f32 v47, v24, v20
	v_lshl_add_u64 v[44:45], v[44:45], 1, s[20:21]
	global_store_dwordx2 v[44:45], v[46:47], off sc1
	v_add_u32_e32 v44, v43, v42
	v_ashrrev_i32_e32 v45, 31, v44
	v_cvt_pk_bf16_f32 v46, v16, v8
	v_cvt_pk_bf16_f32 v47, v4, v0
	v_lshl_add_u64 v[44:45], v[44:45], 1, s[20:21]
	s_and_b64 vcc, exec, s[4:5]
	global_store_dwordx2 v[44:45], v[46:47], off sc1
	s_cbranch_vccnz .LBB0_1184
	v_or_b32_e32 v43, s8, v135
	v_lshl_add_u32 v44, v118, 8, v43
	v_ashrrev_i32_e32 v45, 31, v44
	v_lshl_add_u64 v[44:45], v[44:45], 2, s[22:23]
	global_store_dword v[44:45], v90, off sc1
	v_lshl_add_u32 v44, v30, 8, v43
	v_ashrrev_i32_e32 v45, 31, v44
	v_lshl_add_u64 v[44:45], v[44:45], 2, s[22:23]
	global_store_dword v[44:45], v88, off sc1
	v_lshl_add_u32 v44, v29, 8, v43
	v_ashrrev_i32_e32 v45, 31, v44
	v_lshl_add_u64 v[44:45], v[44:45], 2, s[22:23]
	global_store_dword v[44:45], v80, off sc1
	v_lshl_add_u32 v44, v28, 8, v43
	v_ashrrev_i32_e32 v45, 31, v44
	v_lshl_add_u64 v[44:45], v[44:45], 2, s[22:23]
	global_store_dword v[44:45], v76, off sc1
	v_lshl_add_u32 v44, v120, 8, v43
	v_ashrrev_i32_e32 v45, 31, v44
	v_lshl_add_u64 v[44:45], v[44:45], 2, s[22:23]
	global_store_dword v[44:45], v72, off sc1
	v_lshl_add_u32 v44, v122, 8, v43
	v_ashrrev_i32_e32 v45, 31, v44
	v_lshl_add_u64 v[44:45], v[44:45], 2, s[22:23]
	global_store_dword v[44:45], v68, off sc1
	v_lshl_add_u32 v44, v27, 8, v43
	v_ashrrev_i32_e32 v45, 31, v44
	v_lshl_add_u64 v[44:45], v[44:45], 2, s[22:23]
	global_store_dword v[44:45], v64, off sc1
	v_lshl_add_u32 v44, v26, 8, v43
	v_ashrrev_i32_e32 v45, 31, v44
	v_lshl_add_u64 v[44:45], v[44:45], 2, s[22:23]
	global_store_dword v[44:45], v50, off sc1
	v_lshl_add_u32 v44, v124, 8, v43
	v_ashrrev_i32_e32 v45, 31, v44
	v_lshl_add_u64 v[44:45], v[44:45], 2, s[22:23]
	global_store_dword v[44:45], v38, off sc1
	v_lshl_add_u32 v44, v126, 8, v43
	v_ashrrev_i32_e32 v45, 31, v44
	v_lshl_add_u64 v[44:45], v[44:45], 2, s[22:23]
	global_store_dword v[44:45], v34, off sc1
	v_lshl_add_u32 v44, v15, 8, v43
	v_ashrrev_i32_e32 v45, 31, v44
	v_lshl_add_u64 v[44:45], v[44:45], 2, s[22:23]
	global_store_dword v[44:45], v24, off sc1
	v_lshl_add_u32 v44, v14, 8, v43
	v_ashrrev_i32_e32 v45, 31, v44
	v_lshl_add_u64 v[44:45], v[44:45], 2, s[22:23]
	global_store_dword v[44:45], v20, off sc1
	v_lshl_add_u32 v44, v84, 8, v43
	v_ashrrev_i32_e32 v45, 31, v44
	v_lshl_add_u64 v[44:45], v[44:45], 2, s[22:23]
	global_store_dword v[44:45], v16, off sc1
	v_lshl_add_u32 v44, v104, 8, v43
	v_ashrrev_i32_e32 v45, 31, v44
	v_lshl_add_u64 v[44:45], v[44:45], 2, s[22:23]
	global_store_dword v[44:45], v8, off sc1
	v_lshl_add_u32 v44, v13, 8, v43
	v_ashrrev_i32_e32 v45, 31, v44
	v_lshl_add_u64 v[44:45], v[44:45], 2, s[22:23]
	global_store_dword v[44:45], v4, off sc1
	v_lshl_add_u32 v44, v12, 8, v43
	v_ashrrev_i32_e32 v45, 31, v44
	v_lshl_add_u64 v[44:45], v[44:45], 2, s[22:23]
	global_store_dword v[44:45], v0, off sc1
.LBB0_1184:
	v_or_b32_e32 v44, s71, v137
	v_mul_lo_u32 v44, v44, s74
	v_or_b32_e32 v43, s70, v138
	v_add_u32_e32 v44, 0x200000, v44
	v_cndmask_b32_e64 v43, v43, v44, s[0:1]
	v_add_u32_e32 v44, v43, v31
	v_ashrrev_i32_e32 v45, 31, v44
	v_cvt_pk_bf16_f32 v46, v93, v87
	v_cvt_pk_bf16_f32 v47, v83, v79
	v_lshl_add_u64 v[44:45], v[44:45], 1, s[20:21]
	global_store_dwordx2 v[44:45], v[46:47], off sc1
	v_add_u32_e32 v44, v43, v40
	v_ashrrev_i32_e32 v45, 31, v44
	v_cvt_pk_bf16_f32 v46, v75, v71
	v_cvt_pk_bf16_f32 v47, v67, v53
	v_lshl_add_u64 v[44:45], v[44:45], 1, s[20:21]
	global_store_dwordx2 v[44:45], v[46:47], off sc1
	v_add_u32_e32 v44, v43, v41
	v_ashrrev_i32_e32 v45, 31, v44
	v_cvt_pk_bf16_f32 v46, v49, v37
	v_cvt_pk_bf16_f32 v47, v33, v23
	v_lshl_add_u64 v[44:45], v[44:45], 1, s[20:21]
	global_store_dwordx2 v[44:45], v[46:47], off sc1
	v_add_u32_e32 v44, v43, v42
	v_ashrrev_i32_e32 v45, 31, v44
	v_cvt_pk_bf16_f32 v46, v19, v11
	v_cvt_pk_bf16_f32 v47, v7, v3
	v_lshl_add_u64 v[44:45], v[44:45], 1, s[20:21]
	s_and_b64 vcc, exec, s[4:5]
	global_store_dwordx2 v[44:45], v[46:47], off sc1
	s_cbranch_vccnz .LBB0_1186
	v_or_b32_e32 v43, s8, v137
	v_lshl_add_u32 v44, v118, 8, v43
	v_ashrrev_i32_e32 v45, 31, v44
	v_lshl_add_u64 v[44:45], v[44:45], 2, s[22:23]
	global_store_dword v[44:45], v93, off sc1
	v_lshl_add_u32 v44, v30, 8, v43
	v_ashrrev_i32_e32 v45, 31, v44
	v_lshl_add_u64 v[44:45], v[44:45], 2, s[22:23]
	global_store_dword v[44:45], v87, off sc1
	v_lshl_add_u32 v44, v29, 8, v43
	v_ashrrev_i32_e32 v45, 31, v44
	v_lshl_add_u64 v[44:45], v[44:45], 2, s[22:23]
	global_store_dword v[44:45], v83, off sc1
	v_lshl_add_u32 v44, v28, 8, v43
	v_ashrrev_i32_e32 v45, 31, v44
	v_lshl_add_u64 v[44:45], v[44:45], 2, s[22:23]
	global_store_dword v[44:45], v79, off sc1
	v_lshl_add_u32 v44, v120, 8, v43
	v_ashrrev_i32_e32 v45, 31, v44
	v_lshl_add_u64 v[44:45], v[44:45], 2, s[22:23]
	global_store_dword v[44:45], v75, off sc1
	v_lshl_add_u32 v44, v122, 8, v43
	v_ashrrev_i32_e32 v45, 31, v44
	v_lshl_add_u64 v[44:45], v[44:45], 2, s[22:23]
	global_store_dword v[44:45], v71, off sc1
	v_lshl_add_u32 v44, v27, 8, v43
	v_ashrrev_i32_e32 v45, 31, v44
	v_lshl_add_u64 v[44:45], v[44:45], 2, s[22:23]
	global_store_dword v[44:45], v67, off sc1
	v_lshl_add_u32 v44, v26, 8, v43
	v_ashrrev_i32_e32 v45, 31, v44
	v_lshl_add_u64 v[44:45], v[44:45], 2, s[22:23]
	global_store_dword v[44:45], v53, off sc1
	v_lshl_add_u32 v44, v124, 8, v43
	v_ashrrev_i32_e32 v45, 31, v44
	v_lshl_add_u64 v[44:45], v[44:45], 2, s[22:23]
	global_store_dword v[44:45], v49, off sc1
	v_lshl_add_u32 v44, v126, 8, v43
	v_ashrrev_i32_e32 v45, 31, v44
	v_lshl_add_u64 v[44:45], v[44:45], 2, s[22:23]
	global_store_dword v[44:45], v37, off sc1
	v_lshl_add_u32 v44, v15, 8, v43
	v_ashrrev_i32_e32 v45, 31, v44
	v_lshl_add_u64 v[44:45], v[44:45], 2, s[22:23]
	global_store_dword v[44:45], v33, off sc1
	v_lshl_add_u32 v44, v14, 8, v43
	v_ashrrev_i32_e32 v45, 31, v44
	v_lshl_add_u64 v[44:45], v[44:45], 2, s[22:23]
	global_store_dword v[44:45], v23, off sc1
	v_lshl_add_u32 v44, v84, 8, v43
	v_ashrrev_i32_e32 v45, 31, v44
	v_lshl_add_u64 v[44:45], v[44:45], 2, s[22:23]
	global_store_dword v[44:45], v19, off sc1
	v_lshl_add_u32 v44, v104, 8, v43
	v_ashrrev_i32_e32 v45, 31, v44
	v_lshl_add_u64 v[44:45], v[44:45], 2, s[22:23]
	global_store_dword v[44:45], v11, off sc1
	v_lshl_add_u32 v44, v13, 8, v43
	v_ashrrev_i32_e32 v45, 31, v44
	v_lshl_add_u64 v[44:45], v[44:45], 2, s[22:23]
	global_store_dword v[44:45], v7, off sc1
	v_lshl_add_u32 v44, v12, 8, v43
	v_ashrrev_i32_e32 v45, 31, v44
	v_lshl_add_u64 v[44:45], v[44:45], 2, s[22:23]
	global_store_dword v[44:45], v3, off sc1
.LBB0_1186:
	v_or_b32_e32 v44, s71, v139
	v_mul_lo_u32 v44, v44, s74
	v_or_b32_e32 v43, s70, v140
	v_add_u32_e32 v44, 0x200000, v44
	v_cndmask_b32_e64 v43, v43, v44, s[0:1]
	v_add_u32_e32 v44, v43, v31
	v_ashrrev_i32_e32 v45, 31, v44
	v_cvt_pk_bf16_f32 v46, v92, v86
	v_cvt_pk_bf16_f32 v47, v82, v78
	v_lshl_add_u64 v[44:45], v[44:45], 1, s[20:21]
	global_store_dwordx2 v[44:45], v[46:47], off sc1
	v_add_u32_e32 v44, v43, v40
	v_ashrrev_i32_e32 v45, 31, v44
	v_add_u32_e32 v40, v43, v41
	v_cvt_pk_bf16_f32 v46, v74, v70
	v_cvt_pk_bf16_f32 v47, v66, v52
	v_lshl_add_u64 v[44:45], v[44:45], 1, s[20:21]
	v_ashrrev_i32_e32 v41, 31, v40
	global_store_dwordx2 v[44:45], v[46:47], off sc1
	v_cvt_pk_bf16_f32 v44, v48, v36
	v_cvt_pk_bf16_f32 v45, v32, v22
	v_lshl_add_u64 v[40:41], v[40:41], 1, s[20:21]
	global_store_dwordx2 v[40:41], v[44:45], off sc1
	v_add_u32_e32 v40, v43, v42
	v_ashrrev_i32_e32 v41, 31, v40
	v_cvt_pk_bf16_f32 v42, v18, v10
	v_cvt_pk_bf16_f32 v43, v6, v2
	v_lshl_add_u64 v[40:41], v[40:41], 1, s[20:21]
	s_and_b64 vcc, exec, s[4:5]
	global_store_dwordx2 v[40:41], v[42:43], off sc1
	s_cbranch_vccnz .LBB0_1188
	v_or_b32_e32 v42, s8, v139
	v_lshl_add_u32 v30, v30, 8, v42
	v_ashrrev_i32_e32 v31, 31, v30
	v_lshl_add_u64 v[30:31], v[30:31], 2, s[22:23]
	v_lshl_add_u32 v28, v28, 8, v42
	global_store_dword v[30:31], v86, off sc1
	v_lshl_add_u32 v30, v29, 8, v42
	v_ashrrev_i32_e32 v29, 31, v28
	v_lshl_add_u64 v[28:29], v[28:29], 2, s[22:23]
	global_store_dword v[28:29], v78, off sc1
	v_lshl_add_u32 v28, v120, 8, v42
	v_ashrrev_i32_e32 v29, 31, v28
	v_lshl_add_u64 v[28:29], v[28:29], 2, s[22:23]
	global_store_dword v[28:29], v74, off sc1
	v_lshl_add_u32 v28, v122, 8, v42
	v_ashrrev_i32_e32 v29, 31, v28
	v_lshl_add_u64 v[28:29], v[28:29], 2, s[22:23]
	v_lshl_add_u32 v26, v26, 8, v42
	global_store_dword v[28:29], v70, off sc1
	v_lshl_add_u32 v28, v27, 8, v42
	v_ashrrev_i32_e32 v27, 31, v26
	v_lshl_add_u64 v[26:27], v[26:27], 2, s[22:23]
	global_store_dword v[26:27], v52, off sc1
	v_lshl_add_u32 v26, v124, 8, v42
	v_ashrrev_i32_e32 v27, 31, v26
	v_lshl_add_u64 v[26:27], v[26:27], 2, s[22:23]
	global_store_dword v[26:27], v48, off sc1
	v_lshl_add_u32 v26, v126, 8, v42
	v_ashrrev_i32_e32 v27, 31, v26
	v_lshl_add_u64 v[26:27], v[26:27], 2, s[22:23]
	v_lshl_add_u32 v14, v14, 8, v42
	global_store_dword v[26:27], v36, off sc1
	v_lshl_add_u32 v26, v15, 8, v42
	v_ashrrev_i32_e32 v15, 31, v14
	v_lshl_add_u64 v[14:15], v[14:15], 2, s[22:23]
	global_store_dword v[14:15], v22, off sc1
	v_lshl_add_u32 v14, v84, 8, v42
	v_ashrrev_i32_e32 v15, 31, v14
	v_lshl_add_u64 v[14:15], v[14:15], 2, s[22:23]
	global_store_dword v[14:15], v18, off sc1
	v_lshl_add_u32 v14, v104, 8, v42
	v_ashrrev_i32_e32 v15, 31, v14
	v_lshl_add_u64 v[14:15], v[14:15], 2, s[22:23]
	v_lshl_add_u32 v40, v118, 8, v42
	global_store_dword v[14:15], v10, off sc1
	v_lshl_add_u32 v14, v13, 8, v42
	v_lshl_add_u32 v12, v12, 8, v42
	v_ashrrev_i32_e32 v41, 31, v40
	v_ashrrev_i32_e32 v31, 31, v30
	v_ashrrev_i32_e32 v29, 31, v28
	v_ashrrev_i32_e32 v27, 31, v26
	v_ashrrev_i32_e32 v15, 31, v14
	v_ashrrev_i32_e32 v13, 31, v12
	v_lshl_add_u64 v[40:41], v[40:41], 2, s[22:23]
	v_lshl_add_u64 v[30:31], v[30:31], 2, s[22:23]
	v_lshl_add_u64 v[28:29], v[28:29], 2, s[22:23]
	v_lshl_add_u64 v[26:27], v[26:27], 2, s[22:23]
	v_lshl_add_u64 v[14:15], v[14:15], 2, s[22:23]
	v_lshl_add_u64 v[12:13], v[12:13], 2, s[22:23]
	global_store_dword v[40:41], v92, off sc1
	global_store_dword v[30:31], v82, off sc1
	global_store_dword v[28:29], v66, off sc1
	global_store_dword v[26:27], v32, off sc1
	global_store_dword v[14:15], v6, off sc1
	global_store_dword v[12:13], v2, off sc1

.LBB0_1189:
	s_and_b64 vcc, exec, s[4:5]
	s_cbranch_vccz .LBB0_1170
	v_mov_b32_e32 v12, s82
	ds_read_b64 v[12:13], v12
	s_add_i32 s73, s84, -8
	s_cmp_lt_i32 s85, 64
	s_cselect_b64 s[68:69], -1, 0
	s_and_b64 s[4:5], s[68:69], exec
	s_waitcnt lgkmcnt(0)
	v_readfirstlane_b32 s8, v12
	s_cselect_b32 s4, 0, 0x200
	v_readfirstlane_b32 s70, v13
	s_add_u32 s4, s8, s4
	s_addc_u32 s5, s70, 0
	v_lshlrev_b32_e32 v14, 2, v108
	global_load_dword v13, v14, s[4:5]
	global_load_dword v12, v14, s[4:5] offset:128
	global_load_dword v15, v14, s[4:5] offset:256
	s_nop 0
	global_load_dword v14, v14, s[4:5] offset:384
	v_and_b32_e32 v31, 64, v170
	v_xor_b32_e32 v30, 1, v170
	v_pk_mul_f32 v[26:27], v[90:91], v[90:91]
	v_add_u32_e32 v31, 64, v31
	v_pk_mul_f32 v[28:29], v[92:93], v[92:93]
	v_add_f32_e32 v26, v27, v26
	v_cmp_lt_i32_e32 vcc, v30, v31
	v_add_f32_e32 v26, v26, v29
	v_add_f32_e32 v26, v26, v28
	v_cndmask_b32_e32 v27, v170, v30, vcc
	v_lshlrev_b32_e32 v42, 2, v27
	ds_bpermute_b32 v27, v42, v26
	v_xor_b32_e32 v28, 2, v170
	v_cmp_lt_i32_e32 vcc, v28, v31
	s_or_b64 s[70:71], s[68:69], s[0:1]
	s_lshl_b32 s8, s73, 7
	v_cndmask_b32_e32 v28, v170, v28, vcc
	v_lshlrev_b32_e32 v44, 2, v28
	s_waitcnt lgkmcnt(0)
	v_add_f32_e32 v26, v26, v27
	ds_bpermute_b32 v27, v44, v26
	v_xor_b32_e32 v28, 4, v170
	v_cmp_lt_i32_e32 vcc, v28, v31
	s_waitcnt lgkmcnt(0)
	v_add_f32_e32 v26, v26, v27
	v_cndmask_b32_e32 v28, v170, v28, vcc
	v_lshlrev_b32_e32 v45, 2, v28
	ds_bpermute_b32 v27, v45, v26
	v_xor_b32_e32 v28, 8, v170
	v_cmp_lt_i32_e32 vcc, v28, v31
	s_waitcnt lgkmcnt(0)
	v_add_f32_e32 v26, v26, v27
	v_cndmask_b32_e32 v28, v170, v28, vcc
	v_lshlrev_b32_e32 v46, 2, v28
	ds_bpermute_b32 v27, v46, v26
	v_xor_b32_e32 v28, 16, v170
	v_cmp_lt_i32_e32 vcc, v28, v31
	s_waitcnt lgkmcnt(0)
	v_add_f32_e32 v26, v26, v27
	v_cndmask_b32_e32 v28, v170, v28, vcc
	v_lshlrev_b32_e32 v43, 2, v28
	ds_bpermute_b32 v27, v43, v26
	s_and_b64 vcc, exec, s[70:71]
	s_waitcnt lgkmcnt(0)
	v_add_f32_e32 v26, v26, v27
	v_fmamk_f32 v26, v26, 0x3c000000, v166
	v_rsq_f32_e32 v28, v26
	v_lshl_add_u64 v[26:27], s[8:9], 2, v[116:117]
	s_waitcnt vmcnt(2)
	v_pk_mul_f32 v[30:31], v[12:13], v[28:29] op_sel_hi:[1,0]
	s_nop 0
	v_pk_mul_f32 v[40:41], v[90:91], v[30:31]
	s_waitcnt vmcnt(0)
	v_pk_mul_f32 v[28:29], v[14:15], v[28:29] op_sel_hi:[1,0]
	s_nop 0
	v_pk_mul_f32 v[30:31], v[92:93], v[28:29]
	s_cbranch_vccnz .LBB0_1192
	v_lshlrev_b32_e32 v28, 8, v118
	v_ashrrev_i32_e32 v29, 31, v28
	v_lshl_add_u64 v[28:29], v[28:29], 2, v[26:27]
	global_store_dword v[28:29], v41, off sc1
	global_store_dword v[28:29], v40, off offset:128 sc1
	global_store_dword v[28:29], v31, off offset:256 sc1
	global_store_dword v[28:29], v30, off offset:384 sc1

.LBB0_1194:
	v_pk_mul_f32 v[28:29], v[88:89], v[88:89]
	v_pk_mul_f32 v[54:55], v[86:87], v[86:87]
	v_add_f32_e32 v28, v29, v28
	v_add_f32_e32 v28, v28, v55
	v_add_f32_e32 v28, v28, v54
	ds_bpermute_b32 v29, v42, v28
	s_xor_b64 s[70:71], s[70:71], -1
	s_and_b64 s[0:1], s[68:69], exec
	s_cselect_b32 s0, s83, 0xdf9f000
	s_cselect_b32 s8, s66, s72
	s_waitcnt lgkmcnt(0)
	v_add_f32_e32 v28, v28, v29
	ds_bpermute_b32 v29, v44, v28
	s_cselect_b32 s72, s84, s73
	s_add_u32 s73, s14, s0
	s_addc_u32 s84, s15, 0
	s_and_b64 s[0:1], s[68:69], exec
	s_waitcnt lgkmcnt(0)
	v_add_f32_e32 v47, v28, v29
	ds_bpermute_b32 v54, v45, v47
	s_cselect_b32 s68, 10, 8
	s_lshl_b32 s0, s72, 7
	s_ashr_i32 s1, s0, 31
	s_lshl_b64 s[0:1], s[0:1], 1
	s_waitcnt lgkmcnt(0)
	v_add_f32_e32 v47, v47, v54
	ds_bpermute_b32 v56, v46, v47
	s_add_u32 s0, s73, s0
	v_add_u32_e32 v55, s8, v133
	s_addc_u32 s1, s84, s1
	v_lshlrev_b32_e32 v106, 1, v108
	s_waitcnt lgkmcnt(0)
	v_add_f32_e32 v47, v47, v56
	ds_bpermute_b32 v56, v43, v47
	v_lshlrev_b32_e32 v54, s68, v55
	v_lshl_add_u64 v[28:29], s[0:1], 0, v[106:107]
	v_ashrrev_i32_e32 v55, 31, v54
	v_lshl_add_u64 v[54:55], v[54:55], 1, v[28:29]
	v_cvt_pk_bf16_f32 v40, v40, s0
	global_store_short v[54:55], v40, off offset:64 sc1
	s_waitcnt lgkmcnt(0)
	v_add_f32_e32 v40, v47, v56
	v_fmamk_f32 v40, v40, 0x3c000000, v166
	v_rsq_f32_e32 v40, v40
	v_cvt_pk_bf16_f32 v41, v41, s0
	v_cvt_pk_bf16_f32 v31, v31, s0
	v_cvt_pk_bf16_f32 v30, v30, s0
	global_store_short v[54:55], v41, off sc1
	global_store_short v[54:55], v31, off offset:128 sc1
	global_store_short v[54:55], v30, off offset:192 sc1
	v_pk_mul_f32 v[30:31], v[12:13], v[40:41] op_sel_hi:[1,0]
	v_pk_mul_f32 v[40:41], v[14:15], v[40:41] op_sel_hi:[1,0]
	v_cndmask_b32_e64 v47, 0, 1, s[70:71]
	v_pk_mul_f32 v[30:31], v[88:89], v[30:31]
	v_cmp_ne_u32_e64 s[0:1], 1, v47
	s_andn2_b64 vcc, exec, s[70:71]
	v_pk_mul_f32 v[40:41], v[86:87], v[40:41]
	s_cbranch_vccnz .LBB0_1196
	v_add_lshl_u32 v54, s66, v141, 8
	v_ashrrev_i32_e32 v55, 31, v54
	v_lshl_add_u64 v[54:55], v[54:55], 2, v[26:27]
	global_store_dword v[54:55], v31, off sc1
	global_store_dword v[54:55], v30, off offset:128 sc1
	global_store_dword v[54:55], v41, off offset:256 sc1
	global_store_dword v[54:55], v40, off offset:384 sc1

.LBB0_1198:
	v_pk_mul_f32 v[54:55], v[80:81], v[80:81]
	v_pk_mul_f32 v[56:57], v[82:83], v[82:83]
	v_add_f32_e32 v47, v55, v54
	v_add_f32_e32 v47, v47, v57
	v_add_f32_e32 v47, v47, v56
	ds_bpermute_b32 v54, v42, v47
	v_cvt_pk_bf16_f32 v56, v31, s0
	v_cvt_pk_bf16_f32 v57, v40, s0
	v_add_u32_e32 v55, s8, v141
	v_cvt_pk_bf16_f32 v41, v41, s0
	s_waitcnt lgkmcnt(0)
	v_add_f32_e32 v47, v47, v54
	ds_bpermute_b32 v54, v44, v47
	s_and_b64 vcc, exec, s[0:1]
	s_waitcnt lgkmcnt(0)
	v_add_f32_e32 v47, v47, v54
	ds_bpermute_b32 v54, v45, v47
	s_waitcnt lgkmcnt(0)
	v_add_f32_e32 v31, v47, v54
	ds_bpermute_b32 v47, v46, v31
	v_cvt_pk_bf16_f32 v54, v30, s0
	v_lshlrev_b32_e32 v30, s68, v55
	s_waitcnt lgkmcnt(0)
	v_add_f32_e32 v40, v31, v47
	ds_bpermute_b32 v47, v43, v40
	v_ashrrev_i32_e32 v31, 31, v30
	v_lshl_add_u64 v[30:31], v[30:31], 1, v[28:29]
	global_store_short v[30:31], v56, off sc1
	global_store_short v[30:31], v54, off offset:64 sc1
	global_store_short v[30:31], v41, off offset:128 sc1
	global_store_short v[30:31], v57, off offset:192 sc1
	s_waitcnt lgkmcnt(0)
	v_add_f32_e32 v40, v40, v47
	v_fmamk_f32 v40, v40, 0x3c000000, v166
	v_rsq_f32_e32 v40, v40
	s_nop 0
	v_pk_mul_f32 v[30:31], v[12:13], v[40:41] op_sel_hi:[1,0]
	v_pk_mul_f32 v[54:55], v[14:15], v[40:41] op_sel_hi:[1,0]
	v_pk_mul_f32 v[40:41], v[80:81], v[30:31]
	v_pk_mul_f32 v[30:31], v[82:83], v[54:55]
	s_cbranch_vccnz .LBB0_1200
	v_add_lshl_u32 v54, s66, v142, 8
	v_ashrrev_i32_e32 v55, 31, v54
	v_lshl_add_u64 v[54:55], v[54:55], 2, v[26:27]
	global_store_dword v[54:55], v41, off sc1
	global_store_dword v[54:55], v40, off offset:128 sc1
	global_store_dword v[54:55], v31, off offset:256 sc1
	global_store_dword v[54:55], v30, off offset:384 sc1

.LBB0_1202:
	v_pk_mul_f32 v[54:55], v[76:77], v[76:77]
	v_pk_mul_f32 v[56:57], v[78:79], v[78:79]
	v_add_f32_e32 v47, v55, v54
	v_add_f32_e32 v47, v47, v57
	v_add_f32_e32 v47, v47, v56
	ds_bpermute_b32 v54, v42, v47
	v_cvt_pk_bf16_f32 v56, v40, s0
	v_add_u32_e32 v55, s8, v142
	v_cvt_pk_bf16_f32 v58, v30, s0
	v_lshlrev_b32_e32 v30, s68, v55
	s_waitcnt lgkmcnt(0)
	v_add_f32_e32 v47, v47, v54
	ds_bpermute_b32 v54, v44, v47
	v_cvt_pk_bf16_f32 v57, v31, s0
	v_ashrrev_i32_e32 v31, 31, v30
	v_cvt_pk_bf16_f32 v41, v41, s0
	v_lshl_add_u64 v[30:31], v[30:31], 1, v[28:29]
	s_waitcnt lgkmcnt(0)
	v_add_f32_e32 v47, v47, v54
	ds_bpermute_b32 v54, v45, v47
	global_store_short v[30:31], v41, off sc1
	global_store_short v[30:31], v56, off offset:64 sc1
	global_store_short v[30:31], v57, off offset:128 sc1
	global_store_short v[30:31], v58, off offset:192 sc1
	s_and_b64 vcc, exec, s[0:1]
	s_waitcnt lgkmcnt(0)
	v_add_f32_e32 v47, v47, v54
	ds_bpermute_b32 v54, v46, v47
	s_waitcnt lgkmcnt(0)
	v_add_f32_e32 v40, v47, v54
	ds_bpermute_b32 v47, v43, v40
	s_waitcnt lgkmcnt(0)
	v_add_f32_e32 v40, v40, v47
	v_fmamk_f32 v40, v40, 0x3c000000, v166
	v_rsq_f32_e32 v40, v40
	s_nop 0
	v_pk_mul_f32 v[30:31], v[12:13], v[40:41] op_sel_hi:[1,0]
	v_pk_mul_f32 v[54:55], v[14:15], v[40:41] op_sel_hi:[1,0]
	v_pk_mul_f32 v[40:41], v[76:77], v[30:31]
	v_pk_mul_f32 v[30:31], v[78:79], v[54:55]
	s_cbranch_vccnz .LBB0_1204
	v_add_lshl_u32 v54, s66, v143, 8
	v_ashrrev_i32_e32 v55, 31, v54
	v_lshl_add_u64 v[54:55], v[54:55], 2, v[26:27]
	global_store_dword v[54:55], v41, off sc1
	global_store_dword v[54:55], v40, off offset:128 sc1
	global_store_dword v[54:55], v31, off offset:256 sc1
	global_store_dword v[54:55], v30, off offset:384 sc1

.LBB0_1206:
	v_pk_mul_f32 v[54:55], v[72:73], v[72:73]
	v_pk_mul_f32 v[56:57], v[74:75], v[74:75]
	v_add_f32_e32 v47, v55, v54
	v_add_f32_e32 v47, v47, v57
	v_add_f32_e32 v47, v47, v56
	ds_bpermute_b32 v54, v42, v47
	v_cvt_pk_bf16_f32 v56, v40, s0
	v_add_u32_e32 v55, s8, v143
	v_cvt_pk_bf16_f32 v58, v30, s0
	v_lshlrev_b32_e32 v30, s68, v55
	s_waitcnt lgkmcnt(0)
	v_add_f32_e32 v47, v47, v54
	ds_bpermute_b32 v54, v44, v47
	v_cvt_pk_bf16_f32 v57, v31, s0
	v_ashrrev_i32_e32 v31, 31, v30
	v_cvt_pk_bf16_f32 v41, v41, s0
	v_lshl_add_u64 v[30:31], v[30:31], 1, v[28:29]
	s_waitcnt lgkmcnt(0)
	v_add_f32_e32 v47, v47, v54
	ds_bpermute_b32 v54, v45, v47
	global_store_short v[30:31], v41, off sc1
	global_store_short v[30:31], v56, off offset:64 sc1
	global_store_short v[30:31], v57, off offset:128 sc1
	global_store_short v[30:31], v58, off offset:192 sc1
	s_and_b64 vcc, exec, s[0:1]
	s_waitcnt lgkmcnt(0)
	v_add_f32_e32 v47, v47, v54
	ds_bpermute_b32 v54, v46, v47
	s_waitcnt lgkmcnt(0)
	v_add_f32_e32 v40, v47, v54
	ds_bpermute_b32 v47, v43, v40
	s_waitcnt lgkmcnt(0)
	v_add_f32_e32 v40, v40, v47
	v_fmamk_f32 v40, v40, 0x3c000000, v166
	v_rsq_f32_e32 v40, v40
	s_nop 0
	v_pk_mul_f32 v[30:31], v[12:13], v[40:41] op_sel_hi:[1,0]
	v_pk_mul_f32 v[54:55], v[14:15], v[40:41] op_sel_hi:[1,0]
	v_pk_mul_f32 v[40:41], v[72:73], v[30:31]
	v_pk_mul_f32 v[30:31], v[74:75], v[54:55]
	s_cbranch_vccnz .LBB0_1208
	v_add_lshl_u32 v54, s66, v144, 8
	v_ashrrev_i32_e32 v55, 31, v54
	v_lshl_add_u64 v[54:55], v[54:55], 2, v[26:27]
	global_store_dword v[54:55], v41, off sc1
	global_store_dword v[54:55], v40, off offset:128 sc1
	global_store_dword v[54:55], v31, off offset:256 sc1
	global_store_dword v[54:55], v30, off offset:384 sc1

.LBB0_1210:
	v_pk_mul_f32 v[54:55], v[68:69], v[68:69]
	v_pk_mul_f32 v[56:57], v[70:71], v[70:71]
	v_add_f32_e32 v47, v55, v54
	v_add_f32_e32 v47, v47, v57
	v_add_f32_e32 v47, v47, v56
	ds_bpermute_b32 v54, v42, v47
	v_cvt_pk_bf16_f32 v56, v40, s0
	v_add_u32_e32 v55, s8, v144
	v_cvt_pk_bf16_f32 v58, v30, s0
	v_lshlrev_b32_e32 v30, s68, v55
	s_waitcnt lgkmcnt(0)
	v_add_f32_e32 v47, v47, v54
	ds_bpermute_b32 v54, v44, v47
	v_cvt_pk_bf16_f32 v57, v31, s0
	v_ashrrev_i32_e32 v31, 31, v30
	v_cvt_pk_bf16_f32 v41, v41, s0
	v_lshl_add_u64 v[30:31], v[30:31], 1, v[28:29]
	s_waitcnt lgkmcnt(0)
	v_add_f32_e32 v47, v47, v54
	ds_bpermute_b32 v54, v45, v47
	global_store_short v[30:31], v41, off sc1
	global_store_short v[30:31], v56, off offset:64 sc1
	global_store_short v[30:31], v57, off offset:128 sc1
	global_store_short v[30:31], v58, off offset:192 sc1
	s_and_b64 vcc, exec, s[0:1]
	s_waitcnt lgkmcnt(0)
	v_add_f32_e32 v47, v47, v54
	ds_bpermute_b32 v54, v46, v47
	s_waitcnt lgkmcnt(0)
	v_add_f32_e32 v40, v47, v54
	ds_bpermute_b32 v47, v43, v40
	s_waitcnt lgkmcnt(0)
	v_add_f32_e32 v40, v40, v47
	v_fmamk_f32 v40, v40, 0x3c000000, v166
	v_rsq_f32_e32 v40, v40
	s_nop 0
	v_pk_mul_f32 v[30:31], v[12:13], v[40:41] op_sel_hi:[1,0]
	v_pk_mul_f32 v[54:55], v[14:15], v[40:41] op_sel_hi:[1,0]
	v_pk_mul_f32 v[40:41], v[68:69], v[30:31]
	v_pk_mul_f32 v[30:31], v[70:71], v[54:55]
	s_cbranch_vccnz .LBB0_1212
	v_add_lshl_u32 v54, s66, v145, 8
	v_ashrrev_i32_e32 v55, 31, v54
	v_lshl_add_u64 v[54:55], v[54:55], 2, v[26:27]
	global_store_dword v[54:55], v41, off sc1
	global_store_dword v[54:55], v40, off offset:128 sc1
	global_store_dword v[54:55], v31, off offset:256 sc1
	global_store_dword v[54:55], v30, off offset:384 sc1

.LBB0_1214:
	v_pk_mul_f32 v[54:55], v[64:65], v[64:65]
	v_pk_mul_f32 v[56:57], v[66:67], v[66:67]
	v_add_f32_e32 v47, v55, v54
	v_add_f32_e32 v47, v47, v57
	v_add_f32_e32 v47, v47, v56
	ds_bpermute_b32 v54, v42, v47
	v_cvt_pk_bf16_f32 v56, v40, s0
	v_add_u32_e32 v55, s8, v145
	v_cvt_pk_bf16_f32 v58, v30, s0
	v_lshlrev_b32_e32 v30, s68, v55
	s_waitcnt lgkmcnt(0)
	v_add_f32_e32 v47, v47, v54
	ds_bpermute_b32 v54, v44, v47
	v_cvt_pk_bf16_f32 v57, v31, s0
	v_ashrrev_i32_e32 v31, 31, v30
	v_cvt_pk_bf16_f32 v41, v41, s0
	v_lshl_add_u64 v[30:31], v[30:31], 1, v[28:29]
	s_waitcnt lgkmcnt(0)
	v_add_f32_e32 v47, v47, v54
	ds_bpermute_b32 v54, v45, v47
	global_store_short v[30:31], v41, off sc1
	global_store_short v[30:31], v56, off offset:64 sc1
	global_store_short v[30:31], v57, off offset:128 sc1
	global_store_short v[30:31], v58, off offset:192 sc1
	s_and_b64 vcc, exec, s[0:1]
	s_waitcnt lgkmcnt(0)
	v_add_f32_e32 v47, v47, v54
	ds_bpermute_b32 v54, v46, v47
	s_waitcnt lgkmcnt(0)
	v_add_f32_e32 v40, v47, v54
	ds_bpermute_b32 v47, v43, v40
	s_waitcnt lgkmcnt(0)
	v_add_f32_e32 v40, v40, v47
	v_fmamk_f32 v40, v40, 0x3c000000, v166
	v_rsq_f32_e32 v40, v40
	s_nop 0
	v_pk_mul_f32 v[30:31], v[12:13], v[40:41] op_sel_hi:[1,0]
	v_pk_mul_f32 v[54:55], v[14:15], v[40:41] op_sel_hi:[1,0]
	v_pk_mul_f32 v[40:41], v[64:65], v[30:31]
	v_pk_mul_f32 v[30:31], v[66:67], v[54:55]
	s_cbranch_vccnz .LBB0_1216
	v_add_lshl_u32 v54, s66, v146, 8
	v_ashrrev_i32_e32 v55, 31, v54
	v_lshl_add_u64 v[54:55], v[54:55], 2, v[26:27]
	global_store_dword v[54:55], v41, off sc1
	global_store_dword v[54:55], v40, off offset:128 sc1
	global_store_dword v[54:55], v31, off offset:256 sc1
	global_store_dword v[54:55], v30, off offset:384 sc1

.LBB0_1218:
	v_pk_mul_f32 v[54:55], v[50:51], v[50:51]
	v_pk_mul_f32 v[56:57], v[52:53], v[52:53]
	v_add_f32_e32 v47, v55, v54
	v_add_f32_e32 v47, v47, v57
	v_add_f32_e32 v47, v47, v56
	ds_bpermute_b32 v54, v42, v47
	v_cvt_pk_bf16_f32 v56, v40, s0
	v_add_u32_e32 v55, s8, v146
	v_cvt_pk_bf16_f32 v58, v30, s0
	v_lshlrev_b32_e32 v30, s68, v55
	s_waitcnt lgkmcnt(0)
	v_add_f32_e32 v47, v47, v54
	ds_bpermute_b32 v54, v44, v47
	v_cvt_pk_bf16_f32 v57, v31, s0
	v_ashrrev_i32_e32 v31, 31, v30
	v_cvt_pk_bf16_f32 v41, v41, s0
	v_lshl_add_u64 v[30:31], v[30:31], 1, v[28:29]
	s_waitcnt lgkmcnt(0)
	v_add_f32_e32 v47, v47, v54
	ds_bpermute_b32 v54, v45, v47
	global_store_short v[30:31], v41, off sc1
	global_store_short v[30:31], v56, off offset:64 sc1
	global_store_short v[30:31], v57, off offset:128 sc1
	global_store_short v[30:31], v58, off offset:192 sc1
	s_and_b64 vcc, exec, s[0:1]
	s_waitcnt lgkmcnt(0)
	v_add_f32_e32 v47, v47, v54
	ds_bpermute_b32 v54, v46, v47
	s_waitcnt lgkmcnt(0)
	v_add_f32_e32 v40, v47, v54
	ds_bpermute_b32 v47, v43, v40
	s_waitcnt lgkmcnt(0)
	v_add_f32_e32 v40, v40, v47
	v_fmamk_f32 v40, v40, 0x3c000000, v166
	v_rsq_f32_e32 v40, v40
	s_nop 0
	v_pk_mul_f32 v[30:31], v[12:13], v[40:41] op_sel_hi:[1,0]
	v_pk_mul_f32 v[54:55], v[14:15], v[40:41] op_sel_hi:[1,0]
	v_pk_mul_f32 v[40:41], v[50:51], v[30:31]
	v_pk_mul_f32 v[30:31], v[52:53], v[54:55]
	s_cbranch_vccnz .LBB0_1220
	v_add_lshl_u32 v50, s66, v147, 8
	v_ashrrev_i32_e32 v51, 31, v50
	v_lshl_add_u64 v[50:51], v[50:51], 2, v[26:27]
	global_store_dword v[50:51], v41, off sc1
	global_store_dword v[50:51], v40, off offset:128 sc1
	global_store_dword v[50:51], v31, off offset:256 sc1
	global_store_dword v[50:51], v30, off offset:384 sc1

.LBB0_1222:
	v_pk_mul_f32 v[50:51], v[38:39], v[38:39]
	v_pk_mul_f32 v[52:53], v[48:49], v[48:49]
	v_add_f32_e32 v47, v51, v50
	v_add_f32_e32 v47, v47, v53
	v_add_f32_e32 v47, v47, v52
	ds_bpermute_b32 v50, v42, v47
	v_cvt_pk_bf16_f32 v52, v40, s0
	v_add_u32_e32 v51, s8, v147
	v_cvt_pk_bf16_f32 v54, v30, s0
	v_lshlrev_b32_e32 v30, s68, v51
	s_waitcnt lgkmcnt(0)
	v_add_f32_e32 v47, v47, v50
	ds_bpermute_b32 v50, v44, v47
	v_cvt_pk_bf16_f32 v53, v31, s0
	v_ashrrev_i32_e32 v31, 31, v30
	v_cvt_pk_bf16_f32 v41, v41, s0
	v_lshl_add_u64 v[30:31], v[30:31], 1, v[28:29]
	s_waitcnt lgkmcnt(0)
	v_add_f32_e32 v47, v47, v50
	ds_bpermute_b32 v50, v45, v47
	global_store_short v[30:31], v41, off sc1
	global_store_short v[30:31], v52, off offset:64 sc1
	global_store_short v[30:31], v53, off offset:128 sc1
	global_store_short v[30:31], v54, off offset:192 sc1
	s_and_b64 vcc, exec, s[0:1]
	s_waitcnt lgkmcnt(0)
	v_add_f32_e32 v47, v47, v50
	ds_bpermute_b32 v50, v46, v47
	s_waitcnt lgkmcnt(0)
	v_add_f32_e32 v40, v47, v50
	ds_bpermute_b32 v47, v43, v40
	s_waitcnt lgkmcnt(0)
	v_add_f32_e32 v40, v40, v47
	v_fmamk_f32 v40, v40, 0x3c000000, v166
	v_rsq_f32_e32 v40, v40
	s_nop 0
	v_pk_mul_f32 v[30:31], v[12:13], v[40:41] op_sel_hi:[1,0]
	v_pk_mul_f32 v[40:41], v[14:15], v[40:41] op_sel_hi:[1,0]
	v_pk_mul_f32 v[38:39], v[38:39], v[30:31]
	v_pk_mul_f32 v[30:31], v[48:49], v[40:41]
	s_cbranch_vccnz .LBB0_1224
	v_add_lshl_u32 v40, s66, v148, 8
	v_ashrrev_i32_e32 v41, 31, v40
	v_lshl_add_u64 v[40:41], v[40:41], 2, v[26:27]
	global_store_dword v[40:41], v39, off sc1
	global_store_dword v[40:41], v38, off offset:128 sc1
	global_store_dword v[40:41], v31, off offset:256 sc1
	global_store_dword v[40:41], v30, off offset:384 sc1

.LBB0_1226:
	v_pk_mul_f32 v[40:41], v[34:35], v[34:35]
	v_pk_mul_f32 v[48:49], v[36:37], v[36:37]
	v_add_f32_e32 v40, v41, v40
	v_add_f32_e32 v40, v40, v49
	v_add_f32_e32 v40, v40, v48
	ds_bpermute_b32 v41, v42, v40
	v_cvt_pk_bf16_f32 v48, v38, s0
	v_add_u32_e32 v47, s8, v148
	v_cvt_pk_bf16_f32 v50, v30, s0
	v_lshlrev_b32_e32 v30, s68, v47
	s_waitcnt lgkmcnt(0)
	v_add_f32_e32 v40, v40, v41
	ds_bpermute_b32 v41, v44, v40
	v_cvt_pk_bf16_f32 v49, v31, s0
	v_ashrrev_i32_e32 v31, 31, v30
	v_cvt_pk_bf16_f32 v39, v39, s0
	v_lshl_add_u64 v[30:31], v[30:31], 1, v[28:29]
	s_waitcnt lgkmcnt(0)
	v_add_f32_e32 v40, v40, v41
	ds_bpermute_b32 v41, v45, v40
	global_store_short v[30:31], v39, off sc1
	global_store_short v[30:31], v48, off offset:64 sc1
	global_store_short v[30:31], v49, off offset:128 sc1
	global_store_short v[30:31], v50, off offset:192 sc1
	s_and_b64 vcc, exec, s[0:1]
	s_waitcnt lgkmcnt(0)
	v_add_f32_e32 v40, v40, v41
	ds_bpermute_b32 v41, v46, v40
	s_waitcnt lgkmcnt(0)
	v_add_f32_e32 v38, v40, v41
	ds_bpermute_b32 v40, v43, v38
	s_waitcnt lgkmcnt(0)
	v_add_f32_e32 v38, v38, v40
	v_fmamk_f32 v38, v38, 0x3c000000, v166
	v_rsq_f32_e32 v38, v38
	s_nop 0
	v_pk_mul_f32 v[30:31], v[12:13], v[38:39] op_sel_hi:[1,0]
	v_pk_mul_f32 v[38:39], v[14:15], v[38:39] op_sel_hi:[1,0]
	v_pk_mul_f32 v[34:35], v[34:35], v[30:31]
	v_pk_mul_f32 v[30:31], v[36:37], v[38:39]
	s_cbranch_vccnz .LBB0_1228
	v_add_lshl_u32 v36, s66, v149, 8
	v_ashrrev_i32_e32 v37, 31, v36
	v_lshl_add_u64 v[36:37], v[36:37], 2, v[26:27]
	global_store_dword v[36:37], v35, off sc1
	global_store_dword v[36:37], v34, off offset:128 sc1
	global_store_dword v[36:37], v31, off offset:256 sc1
	global_store_dword v[36:37], v30, off offset:384 sc1

.LBB0_1230:
	v_pk_mul_f32 v[36:37], v[24:25], v[24:25]
	v_pk_mul_f32 v[38:39], v[32:33], v[32:33]
	v_add_f32_e32 v36, v37, v36
	v_add_f32_e32 v36, v36, v39
	v_add_f32_e32 v36, v36, v38
	ds_bpermute_b32 v37, v42, v36
	v_cvt_pk_bf16_f32 v39, v34, s0
	v_add_u32_e32 v38, s8, v149
	v_cvt_pk_bf16_f32 v41, v30, s0
	v_lshlrev_b32_e32 v30, s68, v38
	s_waitcnt lgkmcnt(0)
	v_add_f32_e32 v36, v36, v37
	ds_bpermute_b32 v37, v44, v36
	v_cvt_pk_bf16_f32 v40, v31, s0
	v_ashrrev_i32_e32 v31, 31, v30
	v_cvt_pk_bf16_f32 v35, v35, s0
	v_lshl_add_u64 v[30:31], v[30:31], 1, v[28:29]
	s_waitcnt lgkmcnt(0)
	v_add_f32_e32 v36, v36, v37
	ds_bpermute_b32 v37, v45, v36
	global_store_short v[30:31], v35, off sc1
	global_store_short v[30:31], v39, off offset:64 sc1
	global_store_short v[30:31], v40, off offset:128 sc1
	global_store_short v[30:31], v41, off offset:192 sc1
	s_and_b64 vcc, exec, s[0:1]
	s_waitcnt lgkmcnt(0)
	v_add_f32_e32 v36, v36, v37
	ds_bpermute_b32 v37, v46, v36
	s_waitcnt lgkmcnt(0)
	v_add_f32_e32 v34, v36, v37
	ds_bpermute_b32 v36, v43, v34
	s_waitcnt lgkmcnt(0)
	v_add_f32_e32 v34, v34, v36
	v_fmamk_f32 v34, v34, 0x3c000000, v166
	v_rsq_f32_e32 v34, v34
	s_nop 0
	v_pk_mul_f32 v[30:31], v[12:13], v[34:35] op_sel_hi:[1,0]
	v_pk_mul_f32 v[34:35], v[14:15], v[34:35] op_sel_hi:[1,0]
	v_pk_mul_f32 v[30:31], v[24:25], v[30:31]
	v_pk_mul_f32 v[24:25], v[32:33], v[34:35]
	s_cbranch_vccnz .LBB0_1232
	v_add_lshl_u32 v32, s66, v150, 8
	v_ashrrev_i32_e32 v33, 31, v32
	v_lshl_add_u64 v[32:33], v[32:33], 2, v[26:27]
	global_store_dword v[32:33], v31, off sc1
	global_store_dword v[32:33], v30, off offset:128 sc1
	global_store_dword v[32:33], v25, off offset:256 sc1
	global_store_dword v[32:33], v24, off offset:384 sc1

.LBB0_1234:
	v_pk_mul_f32 v[32:33], v[20:21], v[20:21]
	v_pk_mul_f32 v[34:35], v[22:23], v[22:23]
	v_add_f32_e32 v32, v33, v32
	v_add_f32_e32 v32, v32, v35
	v_add_f32_e32 v32, v32, v34
	ds_bpermute_b32 v33, v42, v32
	v_cvt_pk_bf16_f32 v35, v30, s0
	v_add_u32_e32 v34, s8, v150
	v_cvt_pk_bf16_f32 v37, v24, s0
	v_lshlrev_b32_e32 v24, s68, v34
	s_waitcnt lgkmcnt(0)
	v_add_f32_e32 v32, v32, v33
	ds_bpermute_b32 v33, v44, v32
	v_cvt_pk_bf16_f32 v36, v25, s0
	v_ashrrev_i32_e32 v25, 31, v24
	v_cvt_pk_bf16_f32 v31, v31, s0
	v_lshl_add_u64 v[24:25], v[24:25], 1, v[28:29]
	s_waitcnt lgkmcnt(0)
	v_add_f32_e32 v32, v32, v33
	ds_bpermute_b32 v33, v45, v32
	global_store_short v[24:25], v31, off sc1
	global_store_short v[24:25], v35, off offset:64 sc1
	global_store_short v[24:25], v36, off offset:128 sc1
	global_store_short v[24:25], v37, off offset:192 sc1
	s_and_b64 vcc, exec, s[0:1]
	s_waitcnt lgkmcnt(0)
	v_add_f32_e32 v32, v32, v33
	ds_bpermute_b32 v33, v46, v32
	s_waitcnt lgkmcnt(0)
	v_add_f32_e32 v30, v32, v33
	ds_bpermute_b32 v32, v43, v30
	s_waitcnt lgkmcnt(0)
	v_add_f32_e32 v30, v30, v32
	v_fmamk_f32 v30, v30, 0x3c000000, v166
	v_rsq_f32_e32 v30, v30
	s_nop 0
	v_pk_mul_f32 v[24:25], v[12:13], v[30:31] op_sel_hi:[1,0]
	v_pk_mul_f32 v[30:31], v[14:15], v[30:31] op_sel_hi:[1,0]
	v_pk_mul_f32 v[24:25], v[20:21], v[24:25]
	v_pk_mul_f32 v[20:21], v[22:23], v[30:31]
	s_cbranch_vccnz .LBB0_1236
	v_add_lshl_u32 v22, s66, v151, 8
	v_ashrrev_i32_e32 v23, 31, v22
	v_lshl_add_u64 v[22:23], v[22:23], 2, v[26:27]
	global_store_dword v[22:23], v25, off sc1
	global_store_dword v[22:23], v24, off offset:128 sc1
	global_store_dword v[22:23], v21, off offset:256 sc1
	global_store_dword v[22:23], v20, off offset:384 sc1

.LBB0_1238:
	v_pk_mul_f32 v[22:23], v[16:17], v[16:17]
	v_pk_mul_f32 v[30:31], v[18:19], v[18:19]
	v_add_f32_e32 v22, v23, v22
	v_add_f32_e32 v22, v22, v31
	v_add_f32_e32 v22, v22, v30
	ds_bpermute_b32 v23, v42, v22
	v_add_u32_e32 v30, s8, v151
	v_cvt_pk_bf16_f32 v32, v20, s0
	v_lshlrev_b32_e32 v20, s68, v30
	v_cvt_pk_bf16_f32 v31, v21, s0
	s_waitcnt lgkmcnt(0)
	v_add_f32_e32 v22, v22, v23
	ds_bpermute_b32 v23, v44, v22
	v_ashrrev_i32_e32 v21, 31, v20
	v_cvt_pk_bf16_f32 v25, v25, s0
	v_cvt_pk_bf16_f32 v24, v24, s0
	v_lshl_add_u64 v[20:21], v[20:21], 1, v[28:29]
	s_waitcnt lgkmcnt(0)
	v_add_f32_e32 v22, v22, v23
	ds_bpermute_b32 v23, v45, v22
	global_store_short v[20:21], v25, off sc1
	global_store_short v[20:21], v24, off offset:64 sc1
	global_store_short v[20:21], v31, off offset:128 sc1
	global_store_short v[20:21], v32, off offset:192 sc1
	s_and_b64 vcc, exec, s[0:1]
	s_waitcnt lgkmcnt(0)
	v_add_f32_e32 v22, v22, v23
	ds_bpermute_b32 v23, v46, v22
	s_waitcnt lgkmcnt(0)
	v_add_f32_e32 v22, v22, v23
	ds_bpermute_b32 v23, v43, v22
	s_waitcnt lgkmcnt(0)
	v_add_f32_e32 v22, v22, v23
	v_fmamk_f32 v22, v22, 0x3c000000, v166
	v_rsq_f32_e32 v22, v22
	s_nop 0
	v_pk_mul_f32 v[20:21], v[12:13], v[22:23] op_sel_hi:[1,0]
	v_pk_mul_f32 v[22:23], v[14:15], v[22:23] op_sel_hi:[1,0]
	v_pk_mul_f32 v[20:21], v[16:17], v[20:21]
	v_pk_mul_f32 v[16:17], v[18:19], v[22:23]
	s_cbranch_vccnz .LBB0_1240
	v_add_lshl_u32 v18, s66, v152, 8
	v_ashrrev_i32_e32 v19, 31, v18
	v_lshl_add_u64 v[18:19], v[18:19], 2, v[26:27]
	global_store_dword v[18:19], v21, off sc1
	global_store_dword v[18:19], v20, off offset:128 sc1
	global_store_dword v[18:19], v17, off offset:256 sc1
	global_store_dword v[18:19], v16, off offset:384 sc1

.LBB0_1242:
	v_pk_mul_f32 v[18:19], v[8:9], v[8:9]
	v_pk_mul_f32 v[22:23], v[10:11], v[10:11]
	v_add_f32_e32 v18, v19, v18
	v_add_f32_e32 v18, v18, v23
	v_add_f32_e32 v18, v18, v22
	ds_bpermute_b32 v19, v42, v18
	v_add_u32_e32 v22, s8, v152
	v_cvt_pk_bf16_f32 v24, v16, s0
	v_lshlrev_b32_e32 v16, s68, v22
	v_cvt_pk_bf16_f32 v23, v17, s0
	s_waitcnt lgkmcnt(0)
	v_add_f32_e32 v18, v18, v19
	ds_bpermute_b32 v19, v44, v18
	v_ashrrev_i32_e32 v17, 31, v16
	v_cvt_pk_bf16_f32 v21, v21, s0
	v_cvt_pk_bf16_f32 v20, v20, s0
	v_lshl_add_u64 v[16:17], v[16:17], 1, v[28:29]
	s_waitcnt lgkmcnt(0)
	v_add_f32_e32 v18, v18, v19
	ds_bpermute_b32 v19, v45, v18
	global_store_short v[16:17], v21, off sc1
	global_store_short v[16:17], v20, off offset:64 sc1
	global_store_short v[16:17], v23, off offset:128 sc1
	global_store_short v[16:17], v24, off offset:192 sc1
	s_and_b64 vcc, exec, s[0:1]
	s_waitcnt lgkmcnt(0)
	v_add_f32_e32 v18, v18, v19
	ds_bpermute_b32 v19, v46, v18
	s_waitcnt lgkmcnt(0)
	v_add_f32_e32 v18, v18, v19
	ds_bpermute_b32 v19, v43, v18
	s_waitcnt lgkmcnt(0)
	v_add_f32_e32 v18, v18, v19
	v_fmamk_f32 v18, v18, 0x3c000000, v166
	v_rsq_f32_e32 v18, v18
	s_nop 0
	v_pk_mul_f32 v[16:17], v[12:13], v[18:19] op_sel_hi:[1,0]
	v_pk_mul_f32 v[18:19], v[14:15], v[18:19] op_sel_hi:[1,0]
	v_pk_mul_f32 v[16:17], v[8:9], v[16:17]
	v_pk_mul_f32 v[8:9], v[10:11], v[18:19]
	s_cbranch_vccnz .LBB0_1244
	v_add_lshl_u32 v10, s66, v153, 8
	v_ashrrev_i32_e32 v11, 31, v10
	v_lshl_add_u64 v[10:11], v[10:11], 2, v[26:27]
	global_store_dword v[10:11], v17, off sc1
	global_store_dword v[10:11], v16, off offset:128 sc1
	global_store_dword v[10:11], v9, off offset:256 sc1
	global_store_dword v[10:11], v8, off offset:384 sc1

.LBB0_1246:
	v_pk_mul_f32 v[10:11], v[4:5], v[4:5]
	v_pk_mul_f32 v[18:19], v[6:7], v[6:7]
	v_add_f32_e32 v10, v11, v10
	v_add_f32_e32 v10, v10, v19
	v_add_f32_e32 v10, v10, v18
	ds_bpermute_b32 v11, v42, v10
	v_add_u32_e32 v18, s8, v153
	v_cvt_pk_bf16_f32 v20, v8, s0
	v_lshlrev_b32_e32 v8, s68, v18
	v_cvt_pk_bf16_f32 v19, v9, s0
	s_waitcnt lgkmcnt(0)
	v_add_f32_e32 v10, v10, v11
	ds_bpermute_b32 v11, v44, v10
	v_ashrrev_i32_e32 v9, 31, v8
	v_cvt_pk_bf16_f32 v17, v17, s0
	v_cvt_pk_bf16_f32 v16, v16, s0
	v_lshl_add_u64 v[8:9], v[8:9], 1, v[28:29]
	s_waitcnt lgkmcnt(0)
	v_add_f32_e32 v10, v10, v11
	ds_bpermute_b32 v11, v45, v10
	global_store_short v[8:9], v17, off sc1
	global_store_short v[8:9], v16, off offset:64 sc1
	global_store_short v[8:9], v19, off offset:128 sc1
	global_store_short v[8:9], v20, off offset:192 sc1
	s_and_b64 vcc, exec, s[0:1]
	s_waitcnt lgkmcnt(0)
	v_add_f32_e32 v10, v10, v11
	ds_bpermute_b32 v11, v46, v10
	s_waitcnt lgkmcnt(0)
	v_add_f32_e32 v10, v10, v11
	ds_bpermute_b32 v11, v43, v10
	s_waitcnt lgkmcnt(0)
	v_add_f32_e32 v10, v10, v11
	v_fmamk_f32 v10, v10, 0x3c000000, v166
	v_rsq_f32_e32 v10, v10
	s_nop 0
	v_pk_mul_f32 v[8:9], v[12:13], v[10:11] op_sel_hi:[1,0]
	v_pk_mul_f32 v[10:11], v[14:15], v[10:11] op_sel_hi:[1,0]
	v_pk_mul_f32 v[8:9], v[4:5], v[8:9]
	v_pk_mul_f32 v[4:5], v[6:7], v[10:11]
	s_cbranch_vccnz .LBB0_1248
	v_add_lshl_u32 v6, s66, v154, 8
	v_ashrrev_i32_e32 v7, 31, v6
	v_lshl_add_u64 v[6:7], v[6:7], 2, v[26:27]
	global_store_dword v[6:7], v9, off sc1
	global_store_dword v[6:7], v8, off offset:128 sc1
	global_store_dword v[6:7], v5, off offset:256 sc1
	global_store_dword v[6:7], v4, off offset:384 sc1

.LBB0_1250:
	v_pk_mul_f32 v[6:7], v[0:1], v[0:1]
	v_pk_mul_f32 v[10:11], v[2:3], v[2:3]
	v_add_f32_e32 v6, v7, v6
	v_add_f32_e32 v6, v11, v6
	v_add_f32_e32 v6, v10, v6
	ds_bpermute_b32 v7, v42, v6
	v_add_u32_e32 v10, s8, v154
	v_cvt_pk_bf16_f32 v16, v4, s0
	v_lshlrev_b32_e32 v4, s68, v10
	v_cvt_pk_bf16_f32 v11, v5, s0
	s_waitcnt lgkmcnt(0)
	v_add_f32_e32 v6, v6, v7
	ds_bpermute_b32 v7, v44, v6
	v_ashrrev_i32_e32 v5, 31, v4
	v_cvt_pk_bf16_f32 v9, v9, s0
	v_cvt_pk_bf16_f32 v8, v8, s0
	v_lshl_add_u64 v[4:5], v[4:5], 1, v[28:29]
	s_waitcnt lgkmcnt(0)
	v_add_f32_e32 v6, v6, v7
	ds_bpermute_b32 v7, v45, v6
	global_store_short v[4:5], v9, off sc1
	global_store_short v[4:5], v8, off offset:64 sc1
	global_store_short v[4:5], v11, off offset:128 sc1
	global_store_short v[4:5], v16, off offset:192 sc1
	s_and_b64 vcc, exec, s[0:1]
	s_waitcnt lgkmcnt(0)
	v_add_f32_e32 v6, v6, v7
	ds_bpermute_b32 v7, v46, v6
	s_waitcnt lgkmcnt(0)
	v_add_f32_e32 v6, v6, v7
	ds_bpermute_b32 v7, v43, v6
	s_waitcnt lgkmcnt(0)
	v_add_f32_e32 v6, v6, v7
	v_fmamk_f32 v6, v6, 0x3c000000, v166
	v_rsq_f32_e32 v6, v6
	s_nop 0
	v_pk_mul_f32 v[4:5], v[12:13], v[6:7] op_sel_hi:[1,0]
	v_pk_mul_f32 v[6:7], v[14:15], v[6:7] op_sel_hi:[1,0]
	v_pk_mul_f32 v[4:5], v[0:1], v[4:5]
	v_pk_mul_f32 v[0:1], v[2:3], v[6:7]
	s_cbranch_vccnz .LBB0_1252
	v_add_lshl_u32 v2, s66, v155, 8
	v_ashrrev_i32_e32 v3, 31, v2
	v_lshl_add_u64 v[2:3], v[2:3], 2, v[26:27]
	global_store_dword v[2:3], v5, off sc1
	global_store_dword v[2:3], v4, off offset:128 sc1
	global_store_dword v[2:3], v1, off offset:256 sc1
	global_store_dword v[2:3], v0, off offset:384 sc1

.LBB0_1257:
	v_ashrrev_i32_e32 v9, 31, v2
	v_mov_b32_e32 v8, v2
	v_ashrrev_i32_e32 v11, 31, v3
	v_mov_b32_e32 v10, v3
	v_lshl_add_u64 v[12:13], v[8:9], 2, s[20:21]
	v_lshl_add_u64 v[14:15], v[10:11], 2, s[20:21]
	global_load_dword v16, v[12:13], off
	global_load_dword v17, v[14:15], off
	v_add_u32_sdwa v8, v2, v9 dst_sel:DWORD dst_unused:UNUSED_PAD src0_sel:DWORD src1_sel:BYTE_3
	v_add_u32_sdwa v9, v2, v9 dst_sel:DWORD dst_unused:UNUSED_PAD src0_sel:DWORD src1_sel:WORD_1
	v_add_u32_sdwa v10, v3, v11 dst_sel:DWORD dst_unused:UNUSED_PAD src0_sel:DWORD src1_sel:BYTE_3
	v_add_u32_sdwa v11, v3, v11 dst_sel:DWORD dst_unused:UNUSED_PAD src0_sel:DWORD src1_sel:WORD_1
	v_ashrrev_i32_e32 v12, 8, v8
	v_mul_i32_i24_sdwa v9, sext(v9), s10 dst_sel:DWORD dst_unused:UNUSED_PAD src0_sel:WORD_1 src1_sel:DWORD
	v_ashrrev_i32_e32 v13, 8, v10
	v_and_b32_e32 v8, 0xffffff00, v8
	v_mul_i32_i24_sdwa v11, sext(v11), s10 dst_sel:DWORD dst_unused:UNUSED_PAD src0_sel:WORD_1 src1_sel:DWORD
	v_or_b32_sdwa v9, v9, v12 dst_sel:DWORD dst_unused:UNUSED_PAD src0_sel:DWORD src1_sel:BYTE_0
	v_and_b32_e32 v10, 0xffffff00, v10
	v_sub_u32_e32 v8, v2, v8
	v_or_b32_sdwa v11, v11, v13 dst_sel:DWORD dst_unused:UNUSED_PAD src0_sel:DWORD src1_sel:BYTE_0
	v_lshlrev_b32_e32 v9, 8, v9
	v_add_u32_e32 v5, -2, v5
	v_sub_u32_e32 v10, v3, v10
	v_lshlrev_b32_e32 v11, 8, v11
	v_add3_u32 v8, v9, v8, s11
	v_cmp_eq_u32_e64 s[0:1], 0, v5
	v_add3_u32 v10, v11, v10, s11
	v_ashrrev_i32_e32 v9, 31, v8
	s_or_b64 s[26:27], s[0:1], s[26:27]
	v_add_u32_e32 v3, s9, v3
	v_add_u32_e32 v2, s3, v2
	v_ashrrev_i32_e32 v11, 31, v10
	v_lshl_add_u64 v[8:9], v[8:9], 1, s[22:23]
	v_lshl_add_u64 v[10:11], v[10:11], 1, s[22:23]
	s_waitcnt vmcnt(0)
	v_cvt_pk_bf16_f32 v12, v16, v17
	global_store_short v[8:9], v12, off sc1
	global_store_short_d16_hi v[10:11], v12, off sc1
	s_andn2_b64 exec, exec, s[26:27]
	s_cbranch_execnz .LBB0_1257
	s_or_b64 exec, exec, s[26:27]
	v_mad_u64_u32 v[2:3], s[0:1], v4, s8, v[0:1]
	v_cmp_ne_u32_e64 s[0:1], v6, v4
	s_orn2_b64 s[0:1], s[0:1], exec

.LBB0_1261:
	v_ashrrev_i32_e32 v3, 31, v2
	v_lshl_add_u64 v[4:5], v[2:3], 2, s[20:21]
	global_load_dword v8, v[4:5], off
	v_add_u32_sdwa v4, v2, v3 dst_sel:DWORD dst_unused:UNUSED_PAD src0_sel:DWORD src1_sel:BYTE_3
	v_add_u32_sdwa v3, v2, v3 dst_sel:DWORD dst_unused:UNUSED_PAD src0_sel:DWORD src1_sel:WORD_1
	v_ashrrev_i32_e32 v4, 8, v4
	v_mul_i32_i24_sdwa v3, sext(v3), s3 dst_sel:DWORD dst_unused:UNUSED_PAD src0_sel:WORD_1 src1_sel:DWORD
	v_and_or_b32 v3, v4, s9, v3
	v_mul_i32_i24_e32 v5, 0x100, v4
	v_lshlrev_b32_e32 v3, 8, v3
	v_sub_u32_e32 v3, v3, v5
	v_add3_u32 v4, v2, v3, s10
	v_add_u32_e32 v2, s8, v2
	v_ashrrev_i32_e32 v5, 31, v4
	v_cmp_lt_i32_e64 s[0:1], s11, v2
	v_lshl_add_u64 v[4:5], v[4:5], 1, s[22:23]
	s_or_b64 s[26:27], s[0:1], s[26:27]
	s_waitcnt vmcnt(0)
	v_cvt_pk_bf16_f32 v3, v8, s0
	global_store_short v[4:5], v3, off sc1
	s_andn2_b64 exec, exec, s[26:27]
	s_cbranch_execnz .LBB0_1261

.LBB0_1264:
	v_ashrrev_i32_e32 v11, 31, v4
	v_mov_b32_e32 v10, v4
	v_ashrrev_i32_e32 v13, 31, v5
	v_mov_b32_e32 v12, v5
	v_lshl_add_u64 v[14:15], v[10:11], 2, s[18:19]
	v_lshl_add_u64 v[16:17], v[12:13], 2, s[18:19]
	global_load_dword v1, v[14:15], off
	global_load_dword v18, v[16:17], off
	v_ashrrev_i32_e32 v10, 7, v5
	v_ashrrev_i32_e32 v12, 7, v4
	v_lshrrev_b32_e32 v14, 31, v4
	v_lshrrev_b32_e32 v15, 31, v5
	v_add_u32_e32 v14, v12, v14
	v_add_u32_e32 v15, v10, v15
	v_add_u32_sdwa v16, v4, v11 dst_sel:DWORD dst_unused:UNUSED_PAD src0_sel:DWORD src1_sel:BYTE_3
	v_add_u32_sdwa v17, v5, v13 dst_sel:DWORD dst_unused:UNUSED_PAD src0_sel:DWORD src1_sel:BYTE_3
	v_add_u32_sdwa v11, v4, v11 dst_sel:DWORD dst_unused:UNUSED_PAD src0_sel:DWORD src1_sel:WORD_1
	v_add_u32_sdwa v13, v5, v13 dst_sel:DWORD dst_unused:UNUSED_PAD src0_sel:DWORD src1_sel:WORD_1
	v_and_b32_e32 v14, 0x1fffffe, v14
	v_and_b32_e32 v15, 0x1fffffe, v15
	v_lshlrev_b32_sdwa v11, v8, sext(v11) dst_sel:DWORD dst_unused:UNUSED_PAD src0_sel:DWORD src1_sel:WORD_1
	v_lshlrev_b32_sdwa v13, v8, sext(v13) dst_sel:DWORD dst_unused:UNUSED_PAD src0_sel:DWORD src1_sel:WORD_1
	v_sub_u32_e32 v12, v12, v14
	v_sub_u32_e32 v10, v10, v15
	v_lshl_add_u32 v10, v10, 7, v13
	v_lshl_add_u32 v11, v12, 7, v11
	v_or_b32_e32 v10, v10, v3
	v_or_b32_e32 v11, v11, v2
	v_ashrrev_i32_e32 v16, 8, v16
	v_ashrrev_i32_e32 v17, 8, v17
	v_mul_lo_u32 v10, v10, s10
	v_mul_lo_u32 v11, v11, s10
	v_or_b32_sdwa v12, v10, v17 dst_sel:DWORD dst_unused:UNUSED_PAD src0_sel:DWORD src1_sel:BYTE_0
	v_or_b32_sdwa v10, v11, v16 dst_sel:DWORD dst_unused:UNUSED_PAD src0_sel:DWORD src1_sel:BYTE_0
	v_add_u32_e32 v9, -2, v9
	v_add_u32_e32 v10, 0x200000, v10
	v_cmp_eq_u32_e32 vcc, 0, v9
	v_add_u32_e32 v12, 0x200000, v12
	v_ashrrev_i32_e32 v11, 31, v10
	v_add_u32_e32 v5, s9, v5
	v_add_u32_e32 v4, s3, v4
	s_or_b64 s[22:23], vcc, s[22:23]
	v_ashrrev_i32_e32 v13, 31, v12
	v_lshl_add_u64 v[10:11], v[10:11], 1, s[0:1]
	v_lshl_add_u64 v[12:13], v[12:13], 1, s[0:1]
	s_waitcnt vmcnt(0)
	v_cvt_pk_bf16_f32 v1, v1, v18
	global_store_short v[10:11], v1, off sc1
	global_store_short_d16_hi v[12:13], v1, off sc1
	s_andn2_b64 exec, exec, s[22:23]
	s_cbranch_execnz .LBB0_1264
	s_or_b64 exec, exec, s[22:23]
	v_cmp_ne_u32_e32 vcc, v6, v7
	v_mad_u64_u32 v[0:1], s[10:11], v7, s8, v[0:1]
	s_orn2_b64 s[22:23], vcc, exec

.LBB0_1268:
	global_load_dword v3, v[4:5], off
	v_ashrrev_i32_e32 v6, 7, v0
	v_lshrrev_b32_e32 v7, 31, v0
	v_ashrrev_i32_e32 v8, 31, v0
	v_add_u32_e32 v7, v6, v7
	v_add_u32_sdwa v9, v0, v8 dst_sel:DWORD dst_unused:UNUSED_PAD src0_sel:DWORD src1_sel:BYTE_3
	v_add_u32_sdwa v8, v0, v8 dst_sel:DWORD dst_unused:UNUSED_PAD src0_sel:DWORD src1_sel:WORD_1
	v_and_b32_e32 v7, -2, v7
	v_lshlrev_b32_sdwa v8, v1, v8 dst_sel:DWORD dst_unused:UNUSED_PAD src0_sel:DWORD src1_sel:WORD_1
	v_sub_u32_e32 v6, v6, v7
	v_lshl_add_u32 v6, v6, 7, v8
	v_or_b32_e32 v6, v6, v2
	v_lshrrev_b32_e32 v9, 8, v9
	v_mul_lo_u32 v6, v6, s3
	v_and_or_b32 v6, v9, s9, v6
	v_add_u32_e32 v0, s8, v0
	v_add_u32_e32 v6, 0x200000, v6
	v_cmp_lt_i32_e32 vcc, s10, v0
	v_ashrrev_i32_e32 v7, 31, v6
	v_lshl_add_u64 v[4:5], v[4:5], 0, s[18:19]
	s_or_b64 s[20:21], vcc, s[20:21]
	v_lshl_add_u64 v[6:7], v[6:7], 1, s[0:1]
	s_waitcnt vmcnt(0)
	v_cvt_pk_bf16_f32 v3, v3, s0
	global_store_short v[6:7], v3, off sc1
	s_andn2_b64 exec, exec, s[20:21]
	s_cbranch_execnz .LBB0_1268

.LBB0_1270:
	s_cmp_gt_i32 s17, 15
	s_cselect_b64 s[4:5], -1, 0
	s_and_b64 s[0:1], s[6:7], s[4:5]
	s_andn2_b64 vcc, exec, s[0:1]
	s_cbranch_vccnz .LBB0_1282
	s_waitcnt vmcnt(0)
	v_or_b32_e32 v0, v201, v200
	s_movk_i32 s0, 0x3ff
	v_and_or_b32 v0, v0, s0, v199
	v_cmp_eq_u32_e32 vcc, 0, v0
	s_waitcnt lgkmcnt(0)
	s_barrier
	s_and_saveexec_b64 s[0:1], vcc
	s_cbranch_execz .LBB0_1281
	s_add_u32 s6, s14, 0x5be8c00
	s_addc_u32 s7, s15, 0
	s_lshl_b32 s3, s2, 1
	v_mov_b32_e32 v0, s3
	v_mov_b32_e32 v1, 0x930f
	global_store_short v0, v1, s[6:7] sc1
	s_cmp_lg_u32 s2, 0
	s_cbranch_scc1 .Lgbar_wait_14
	s_lshr_b32 s3, s33, 3
	s_bfm_b64 s[8:9], s3, 0
	s_cmpk_gt_u32 s33, 0x1ff
	s_cselect_b64 s[8:9], -1, s[8:9]
	s_mov_b64 exec, -1
	v_mbcnt_lo_u32_b32 v229, -1, 0
	v_mbcnt_hi_u32_b32 v229, -1, v229
	v_lshlrev_b32_e32 v229, 4, v229
	s_mov_b32 s10, 0x930f930f
	s_mov_b64 exec, s[8:9]

.LBB0_1285:
	v_pk_fma_f32 v[64:65], v[64:65], s[18:19], v[152:153] op_sel_hi:[1,0,1] neg_lo:[0,0,1] neg_hi:[0,0,1]
	v_pk_fma_f32 v[72:73], v[72:73], s[18:19], v[152:153] op_sel_hi:[1,0,1] neg_lo:[0,0,1] neg_hi:[0,0,1]
	v_exp_f32_e32 v98, v64
	v_exp_f32_e32 v99, v65
	v_pk_fma_f32 v[64:65], v[66:67], s[18:19], v[152:153] op_sel_hi:[1,0,1] neg_lo:[0,0,1] neg_hi:[0,0,1]
	ds_read_b128 v[82:85], v171 offset:17504
	v_exp_f32_e32 v100, v64
	v_exp_f32_e32 v101, v65
	v_pk_fma_f32 v[64:65], v[68:69], s[18:19], v[152:153] op_sel_hi:[1,0,1] neg_lo:[0,0,1] neg_hi:[0,0,1]
	v_pk_fma_f32 v[68:69], v[70:71], s[18:19], v[152:153] op_sel_hi:[1,0,1] neg_lo:[0,0,1] neg_hi:[0,0,1]
	v_exp_f32_e32 v102, v64
	v_exp_f32_e32 v103, v65
	ds_read_b128 v[64:67], v171 offset:17472
	v_exp_f32_e32 v104, v68
	v_exp_f32_e32 v105, v69
	v_cvt_pk_bf16_f32 v68, v98, v99
	v_cvt_pk_bf16_f32 v69, v100, v101
	v_cvt_pk_bf16_f32 v70, v102, v103
	v_cvt_pk_bf16_f32 v71, v104, v105
	v_exp_f32_e32 v72, v72
	v_exp_f32_e32 v73, v73
	s_waitcnt lgkmcnt(0)
	v_mfma_f32_32x32x16_bf16 v[48:63], v[64:67], v[68:71], v[48:63]
	ds_read_b128 v[64:67], v171 offset:22080
	ds_read_b128 v[86:89], v171 offset:22112
	s_lshl_b32 s8, s24, 1
	s_add_i32 s41, s41, s33
	s_cmpk_gt_i32 s41, 0x3ff
	s_waitcnt lgkmcnt(1)
	v_mfma_f32_32x32x16_bf16 v[32:47], v[64:67], v[68:71], v[32:47]
	ds_read_b128 v[64:67], v171 offset:26688
	ds_read_b128 v[90:93], v171 offset:31296
	ds_read_b128 v[94:97], v171 offset:26720
	s_waitcnt lgkmcnt(2)
	v_mfma_f32_32x32x16_bf16 v[16:31], v[64:67], v[68:71], v[16:31]
	v_fma_f32 v64, v74, s18, -v152
	v_fma_f32 v65, v75, s18, -v153
	v_exp_f32_e32 v74, v64
	v_exp_f32_e32 v75, v65
	v_pk_fma_f32 v[64:65], v[76:77], s[18:19], v[152:153] op_sel_hi:[1,0,1] neg_lo:[0,0,1] neg_hi:[0,0,1]
	s_nop 0
	v_exp_f32_e32 v76, v64
	s_waitcnt lgkmcnt(1)
	v_mfma_f32_32x32x16_bf16 v[0:15], v[90:93], v[68:71], v[0:15]
	v_fma_f32 v68, v78, s18, -v152
	v_fma_f32 v69, v79, s18, -v153
	v_exp_f32_e32 v77, v65
	v_exp_f32_e32 v78, v68
	v_exp_f32_e32 v79, v69
	v_cvt_pk_bf16_f32 v68, v72, v73
	v_cvt_pk_bf16_f32 v69, v74, v75
	v_cvt_pk_bf16_f32 v70, v76, v77
	v_cvt_pk_bf16_f32 v71, v78, v79
	ds_read_b128 v[64:67], v171 offset:31328
	s_nop 0
	v_mfma_f32_32x32x16_bf16 v[48:63], v[82:85], v[68:71], v[48:63]
	v_add_f32_e64 v82, v98, 0
	v_add_f32_e64 v83, v99, 0
	v_add_f32_e64 v82, v100, v82
	v_add_f32_e64 v83, v101, v83
	v_add_f32_e64 v82, v102, v82
	v_add_f32_e64 v83, v103, v83
	v_pk_add_f32 v[82:83], v[104:105], v[82:83]
	v_mfma_f32_32x32x16_bf16 v[32:47], v[86:89], v[68:71], v[32:47]
	v_add_f32_e64 v72, v72, v82
	v_add_f32_e64 v73, v73, v83
	v_add_f32_e64 v72, v74, v72
	v_add_f32_e64 v73, v75, v73
	v_add_f32_e64 v72, v76, v72
	v_add_f32_e64 v73, v77, v73
	v_pk_add_f32 v[72:73], v[78:79], v[72:73]
	s_waitcnt lgkmcnt(1)
	v_mfma_f32_32x32x16_bf16 v[16:31], v[94:97], v[68:71], v[16:31]
	v_add_f32_e32 v72, v72, v73
	v_add_f32_e32 v74, v80, v72
	ds_bpermute_b32 v75, v168, v74
	v_lshl_add_u64 v[72:73], s[6:7], 0, v[150:151]
	v_lshl_add_u64 v[72:73], v[72:73], 0, s[8:9]
	s_waitcnt lgkmcnt(0)
	v_add_f32_e32 v74, v74, v75
	v_div_scale_f32 v75, s[26:27], v74, v74, 1.0
	v_rcp_f32_e32 v76, v75
	v_mfma_f32_32x32x16_bf16 v[0:15], v[64:67], v[68:71], v[0:15]
	v_fma_f32 v64, -v75, v76, 1.0
	v_fmac_f32_e32 v76, v64, v76
	v_div_scale_f32 v64, vcc, 1.0, v74, 1.0
	v_mul_f32_e32 v65, v64, v76
	v_fma_f32 v66, -v75, v65, v64
	v_fmac_f32_e32 v65, v66, v76
	v_fma_f32 v64, -v75, v65, v64
	v_div_fmas_f32 v64, v64, v76, v65
	v_div_fixup_f32 v64, v64, v74, 1.0
	v_pk_mul_f32 v[48:49], v[48:49], v[64:65] op_sel_hi:[1,0]
	v_pk_mul_f32 v[50:51], v[50:51], v[64:65] op_sel_hi:[1,0]
	v_pk_mul_f32 v[32:33], v[32:33], v[64:65] op_sel_hi:[1,0]
	v_pk_mul_f32 v[34:35], v[34:35], v[64:65] op_sel_hi:[1,0]
	v_pk_mul_f32 v[16:17], v[16:17], v[64:65] op_sel_hi:[1,0]
	v_pk_mul_f32 v[18:19], v[18:19], v[64:65] op_sel_hi:[1,0]
	v_pk_mul_f32 v[0:1], v[0:1], v[64:65] op_sel_hi:[1,0]
	v_pk_mul_f32 v[2:3], v[2:3], v[64:65] op_sel_hi:[1,0]
	v_pk_mul_f32 v[52:53], v[52:53], v[64:65] op_sel_hi:[1,0]
	v_pk_mul_f32 v[54:55], v[54:55], v[64:65] op_sel_hi:[1,0]
	v_pk_mul_f32 v[56:57], v[56:57], v[64:65] op_sel_hi:[1,0]
	v_pk_mul_f32 v[58:59], v[58:59], v[64:65] op_sel_hi:[1,0]
	v_pk_mul_f32 v[60:61], v[60:61], v[64:65] op_sel_hi:[1,0]
	v_pk_mul_f32 v[62:63], v[62:63], v[64:65] op_sel_hi:[1,0]
	v_pk_mul_f32 v[36:37], v[36:37], v[64:65] op_sel_hi:[1,0]
	v_pk_mul_f32 v[38:39], v[38:39], v[64:65] op_sel_hi:[1,0]
	v_pk_mul_f32 v[40:41], v[40:41], v[64:65] op_sel_hi:[1,0]
	v_pk_mul_f32 v[42:43], v[42:43], v[64:65] op_sel_hi:[1,0]
	v_pk_mul_f32 v[44:45], v[44:45], v[64:65] op_sel_hi:[1,0]
	v_pk_mul_f32 v[46:47], v[46:47], v[64:65] op_sel_hi:[1,0]
	v_pk_mul_f32 v[20:21], v[20:21], v[64:65] op_sel_hi:[1,0]
	v_pk_mul_f32 v[22:23], v[22:23], v[64:65] op_sel_hi:[1,0]
	v_pk_mul_f32 v[24:25], v[24:25], v[64:65] op_sel_hi:[1,0]
	v_pk_mul_f32 v[26:27], v[26:27], v[64:65] op_sel_hi:[1,0]
	v_pk_mul_f32 v[28:29], v[28:29], v[64:65] op_sel_hi:[1,0]
	v_pk_mul_f32 v[30:31], v[30:31], v[64:65] op_sel_hi:[1,0]
	v_pk_mul_f32 v[4:5], v[4:5], v[64:65] op_sel_hi:[1,0]
	v_pk_mul_f32 v[6:7], v[6:7], v[64:65] op_sel_hi:[1,0]
	v_pk_mul_f32 v[8:9], v[8:9], v[64:65] op_sel_hi:[1,0]
	v_pk_mul_f32 v[10:11], v[10:11], v[64:65] op_sel_hi:[1,0]
	v_pk_mul_f32 v[12:13], v[12:13], v[64:65] op_sel_hi:[1,0]
	v_pk_mul_f32 v[14:15], v[14:15], v[64:65] op_sel_hi:[1,0]
	v_lshl_add_u64 v[64:65], v[72:73], 0, v[144:145]
	v_cvt_pk_bf16_f32 v48, v48, v49
	v_cvt_pk_bf16_f32 v49, v50, v51
	v_cvt_pk_bf16_f32 v32, v32, v33
	v_cvt_pk_bf16_f32 v33, v34, v35
	v_cvt_pk_bf16_f32 v16, v16, v17
	v_cvt_pk_bf16_f32 v17, v18, v19
	v_cvt_pk_bf16_f32 v0, v0, v1
	v_cvt_pk_bf16_f32 v1, v2, v3
	global_store_dwordx2 v[64:65], v[48:49], off sc1
	v_cvt_pk_bf16_f32 v48, v52, v53
	v_cvt_pk_bf16_f32 v49, v54, v55
	global_store_dwordx2 v[64:65], v[32:33], off offset:64 sc1
	v_cvt_pk_bf16_f32 v32, v36, v37
	v_cvt_pk_bf16_f32 v33, v38, v39
	global_store_dwordx2 v[64:65], v[16:17], off offset:128 sc1
	v_cvt_pk_bf16_f32 v16, v20, v21
	v_cvt_pk_bf16_f32 v17, v22, v23
	global_store_dwordx2 v[64:65], v[0:1], off offset:192 sc1
	v_cvt_pk_bf16_f32 v0, v4, v5
	v_cvt_pk_bf16_f32 v1, v6, v7
	global_store_dwordx2 v[64:65], v[48:49], off offset:16 sc1
	v_cvt_pk_bf16_f32 v48, v56, v57
	v_cvt_pk_bf16_f32 v49, v58, v59
	global_store_dwordx2 v[64:65], v[32:33], off offset:80 sc1
	v_cvt_pk_bf16_f32 v32, v40, v41
	v_cvt_pk_bf16_f32 v33, v42, v43
	global_store_dwordx2 v[64:65], v[16:17], off offset:144 sc1
	v_cvt_pk_bf16_f32 v16, v24, v25
	v_cvt_pk_bf16_f32 v17, v26, v27
	global_store_dwordx2 v[64:65], v[0:1], off offset:208 sc1
	v_cvt_pk_bf16_f32 v0, v8, v9
	v_cvt_pk_bf16_f32 v1, v10, v11
	global_store_dwordx2 v[64:65], v[48:49], off offset:32 sc1
	v_cvt_pk_bf16_f32 v48, v60, v61
	v_cvt_pk_bf16_f32 v49, v62, v63
	global_store_dwordx2 v[64:65], v[32:33], off offset:96 sc1
	v_cvt_pk_bf16_f32 v32, v44, v45
	v_cvt_pk_bf16_f32 v33, v46, v47
	global_store_dwordx2 v[64:65], v[16:17], off offset:160 sc1
	v_cvt_pk_bf16_f32 v16, v28, v29
	v_cvt_pk_bf16_f32 v17, v30, v31
	global_store_dwordx2 v[64:65], v[0:1], off offset:224 sc1
	v_cvt_pk_bf16_f32 v0, v12, v13
	v_cvt_pk_bf16_f32 v1, v14, v15
	global_store_dwordx2 v[64:65], v[48:49], off offset:48 sc1
	global_store_dwordx2 v[64:65], v[32:33], off offset:112 sc1
	global_store_dwordx2 v[64:65], v[16:17], off offset:176 sc1
	global_store_dwordx2 v[64:65], v[0:1], off offset:240 sc1
	s_cbranch_scc1 .LBB0_1306

.LBB0_1306:
	s_cmp_gt_i32 s17, 16
	s_cselect_b64 s[6:7], -1, 0
	s_and_b64 s[0:1], s[0:1], s[6:7]
	s_andn2_b64 vcc, exec, s[0:1]
	s_cbranch_vccnz .LBB0_1318
	s_waitcnt vmcnt(0)
	v_or_b32_e32 v0, v201, v200
	s_movk_i32 s0, 0x3ff
	v_and_or_b32 v0, v0, s0, v199
	v_cmp_eq_u32_e32 vcc, 0, v0
	s_waitcnt lgkmcnt(0)
	s_barrier
	s_and_saveexec_b64 s[0:1], vcc
	s_cbranch_execz .LBB0_1317
	s_add_u32 s4, s14, 0x5be8c00
	s_addc_u32 s5, s15, 0
	s_lshl_b32 s3, s2, 1
	v_mov_b32_e32 v0, s3
	v_mov_b32_e32 v1, 0x9310
	global_store_short v0, v1, s[4:5] sc1
	s_cmp_lg_u32 s2, 0
	s_cbranch_scc1 .Lgbar_wait_15
	s_lshr_b32 s3, s33, 3
	s_bfm_b64 s[8:9], s3, 0
	s_cmpk_gt_u32 s33, 0x1ff
	s_cselect_b64 s[8:9], -1, s[8:9]
	s_mov_b64 exec, -1
	v_mbcnt_lo_u32_b32 v229, -1, 0
	v_mbcnt_hi_u32_b32 v229, -1, v229
	v_lshlrev_b32_e32 v229, 4, v229
	s_mov_b32 s10, 0x93109310
	s_mov_b64 exec, s[8:9]

.LBB0_1318:
	s_cmp_lt_i32 s16, 17
	s_cselect_b64 s[4:5], -1, 0
	s_and_b64 s[0:1], s[4:5], s[6:7]
	s_andn2_b64 vcc, exec, s[0:1]
	s_cbranch_vccnz .LBB0_1358
	s_ashr_i32 s0, s2, 31
	s_and_b32 s0, s0, s33
	s_add_i32 s3, s0, s2
	s_cmpk_gt_i32 s3, 0x3ff
	s_cbranch_scc1 .LBB0_1358
	v_lshrrev_b32_e32 v0, 3, v199
	s_waitcnt lgkmcnt(0)
	v_lshrrev_b32_e32 v1, 5, v199
	v_bfe_u32 v4, v199, 1, 3
	v_lshlrev_b32_e32 v5, 4, v199
	v_bfe_u32 v2, v199, 5, 1
	v_xor_b32_e32 v6, v5, v199
	v_lshlrev_b32_e32 v7, 11, v0
	s_movk_i32 s0, 0x70
	v_bitop3_b32 v1, v1, v4, 1 bitop3:0x6c
	v_and_or_b32 v64, v6, s0, v7
	v_lshlrev_b32_e32 v7, 4, v1
	v_bitop3_b32 v1, v2, v4, 2 bitop3:0x36
	v_lshrrev_b32_e32 v3, 1, v199
	v_lshlrev_b32_e32 v9, 4, v1
	v_bitop3_b32 v1, v2, v4, 4 bitop3:0x36
	v_mov_b32_e32 v65, 0
	v_and_b32_e32 v3, 0x1e0, v3
	v_lshlrev_b32_e32 v10, 4, v1
	v_bitop3_b32 v1, v2, v4, 6 bitop3:0x36
	s_waitcnt vmcnt(25)
	v_and_b32_e32 v138, 31, v199
	v_lshlrev_b32_e32 v2, 4, v1
	v_and_or_b32 v139, v0, 4, v3
	v_lshl_add_u64 v[0:1], s[14:15], 0, v[64:65]
	s_mov_b64 s[8:9], 0xb79f000
	s_add_u32 s10, s14, 0x5c4e000
	v_or_b32_e32 v6, v3, v138
	v_lshl_add_u64 v[66:67], v[0:1], 0, s[8:9]
	s_mov_b64 s[8:9], 0x10a0000
	s_addc_u32 s11, s15, 0
	v_lshl_add_u32 v6, v6, 7, 0
	v_lshl_add_u32 v8, v138, 7, 0
	v_lshl_add_u64 v[68:69], v[0:1], 0, s[8:9]
	s_add_u32 s8, s14, 0x679f000
	v_add_u32_e32 v140, 0, v5
	v_mbcnt_lo_u32_b32 v0, -1, 0
	s_mov_b32 s7, 0
	v_cmp_eq_u32_e64 s[0:1], 0, v138
	s_addc_u32 s9, s15, 0
	v_add_u32_e32 v141, 0x4000, v140
	s_mov_b64 s[18:19], 0x10000
	v_add_u32_e32 v142, 0x1000, v140
	v_add_u32_e32 v143, 0x5000, v140
	s_mov_b64 s[20:21], 0x20000
	s_waitcnt vmcnt(24)
	v_add_u32_e32 v144, 0x2000, v140
	v_add_u32_e32 v145, 0x6000, v140
	s_mov_b64 s[22:23], 0x30000
	v_add_u32_e32 v146, 0x3000, v140
	v_add_u32_e32 v147, 0x7000, v140
	s_mov_b64 s[24:25], 0xb79f080
	s_mov_b64 s[26:27], 0x10a0080
	v_add_u32_e32 v148, 0x8000, v140
	v_add_u32_e32 v149, 0xc000, v140
	s_mov_b64 s[28:29], 0xb7af080
	v_add_u32_e32 v150, 0x9000, v140
	s_mov_b64 s[30:31], 0x10b0080
	v_add_u32_e32 v151, 0xd000, v140
	s_mov_b64 s[34:35], 0xb7bf080
	s_waitcnt vmcnt(23)
	v_add_u32_e32 v152, 0xa000, v140
	s_mov_b64 s[36:37], 0x10c0080
	v_add_u32_e32 v153, 0xe000, v140
	s_mov_b64 s[38:39], 0xb7cf080
	v_add_u32_e32 v154, 0xb000, v140
	s_mov_b64 s[40:41], 0x10d0080
	v_add_u32_e32 v155, 0xf000, v140
	s_waitcnt vmcnt(22)
	v_add_u32_e32 v156, v6, v7
	v_add_u32_e32 v157, v8, v7
	v_add_u32_e32 v158, v6, v9
	v_add_u32_e32 v159, v8, v9
	s_waitcnt vmcnt(21)
	v_add_u32_e32 v160, v6, v10
	v_add_u32_e32 v161, v8, v10
	v_add_u32_e32 v162, v6, v2
	v_add_u32_e32 v163, v8, v2
	s_mov_b64 s[42:43], 0xb79f100
	s_mov_b64 s[44:45], 0x10a0100
	s_mov_b64 s[46:47], 0xb7af100
	s_mov_b64 s[48:49], 0x10b0100
	s_mov_b64 s[50:51], 0xb7bf100
	s_mov_b64 s[52:53], 0x10c0100
	s_mov_b64 s[54:55], 0xb7cf100
	s_mov_b64 s[56:57], 0x10d0100
	s_add_i32 s70, 0, 0x12070
	s_waitcnt vmcnt(19)
	v_mbcnt_hi_u32_b32 v164, -1, v0
	s_mov_b32 s39, 0
	s_branch .LBB0_1322

.LBB0_1322:
	s_ashr_i32 s6, s3, 31
	s_lshr_b32 s6, s6, 26
	s_add_i32 s6, s3, s6
	s_ashr_i32 s58, s6, 6
	s_andn2_b32 s6, s6, 63
	s_sub_i32 s6, s3, s6
	s_ashr_i32 s59, s6, 31
	s_lshr_b32 s59, s59, 29
	s_add_i32 s59, s6, s59
	s_ashr_i32 s64, s59, 3
	s_and_b32 s59, s59, -8
	s_lshl_b32 s58, s58, 3
	s_sub_i32 s6, s6, s59
	s_add_i32 s6, s6, s58
	s_lshl_b32 s66, s6, 7
	s_ashr_i32 s67, s66, 31
	s_lshl_b32 s68, s64, 7
	s_lshl_b64 s[58:59], s[66:67], 11
	s_ashr_i32 s69, s68, 31
	s_cmp_eq_u32 s39, 1
	s_cbranch_scc1 .Lgk_pfhead_p16
	s_lshl_b32 s38, s66, 11
	s_add_u32 s18, s14, s38
	s_addc_u32 s19, s15, 0
	s_add_u32 s18, s18, 0xb79f000
	s_addc_u32 s19, s19, 0
	s_add_u32 s20, s18, 0x10000
	s_addc_u32 s21, s19, 0
	s_add_u32 s22, s20, 0x10000
	s_addc_u32 s23, s21, 0
	s_add_u32 s24, s22, 0x10000
	s_addc_u32 s25, s23, 0
	s_lshl_b32 s38, s68, 11
	s_add_u32 s26, s14, s38
	s_addc_u32 s27, s15, 0
	s_add_u32 s26, s26, 0x10a0000
	s_addc_u32 s27, s27, 0
	s_add_u32 s28, s26, 0x10000
	s_addc_u32 s29, s27, 0
	s_add_u32 s30, s28, 0x10000
	s_addc_u32 s31, s29, 0
	s_add_u32 s34, s30, 0x10000
	s_addc_u32 s35, s31, 0
	v_readfirstlane_b32 s36, v140
	v_mov_b32_e32 v254, v64
	s_mov_b32 m0, s36
	s_nop 0
	global_load_lds_dwordx4 v254, s[18:19]
	s_add_u32 m0, m0, 0x1000
	s_nop 0
	global_load_lds_dwordx4 v254, s[20:21]
	s_add_u32 m0, m0, 0x1000
	s_nop 0
	global_load_lds_dwordx4 v254, s[22:23]
	s_add_u32 m0, m0, 0x1000
	s_nop 0
	global_load_lds_dwordx4 v254, s[24:25]
	s_add_u32 m0, m0, 0x1000
	s_nop 0
	global_load_lds_dwordx4 v254, s[26:27]
	s_add_u32 m0, m0, 0x1000
	s_nop 0
	global_load_lds_dwordx4 v254, s[28:29]
	s_add_u32 m0, m0, 0x1000
	s_nop 0
	global_load_lds_dwordx4 v254, s[30:31]
	s_add_u32 m0, m0, 0x1000
	s_nop 0
	global_load_lds_dwordx4 v254, s[34:35]
	v_add_u32_e32 v254, 0x80, v254
	s_add_u32 m0, s36, 0x8000
	s_nop 0
	global_load_lds_dwordx4 v254, s[18:19]
	s_add_u32 m0, m0, 0x1000
	s_nop 0
	global_load_lds_dwordx4 v254, s[20:21]
	s_add_u32 m0, m0, 0x1000
	s_nop 0
	global_load_lds_dwordx4 v254, s[22:23]
	s_add_u32 m0, m0, 0x1000
	s_nop 0
	global_load_lds_dwordx4 v254, s[24:25]
	s_add_u32 m0, m0, 0x1000
	s_nop 0
	global_load_lds_dwordx4 v254, s[26:27]
	s_add_u32 m0, m0, 0x1000
	s_nop 0
	global_load_lds_dwordx4 v254, s[28:29]
	s_add_u32 m0, m0, 0x1000
	s_nop 0
	global_load_lds_dwordx4 v254, s[30:31]
	s_add_u32 m0, m0, 0x1000
	s_nop 0
	global_load_lds_dwordx4 v254, s[34:35]
	v_add_u32_e32 v254, 0x80, v254

.LBB0_1322_pf_p16:
	s_ashr_i32 s41, s40, 31
	s_lshr_b32 s41, s41, 26
	s_add_i32 s41, s40, s41
	s_ashr_i32 s42, s41, 6
	s_andn2_b32 s41, s41, 63
	s_sub_i32 s41, s40, s41
	s_ashr_i32 s43, s41, 31
	s_lshr_b32 s43, s43, 29
	s_add_i32 s43, s41, s43
	s_ashr_i32 s46, s43, 3
	s_and_b32 s43, s43, -8
	s_lshl_b32 s42, s42, 3
	s_sub_i32 s41, s41, s43
	s_add_i32 s41, s41, s42
	s_lshl_b32 s44, s41, 7
	s_ashr_i32 s45, s44, 31
	s_lshl_b32 s47, s46, 7
	s_lshl_b64 s[42:43], s[44:45], 11
	s_ashr_i32 s48, s47, 31
	s_lshl_b32 s38, s44, 11
	s_add_u32 s18, s14, s38
	s_addc_u32 s19, s15, 0
	s_add_u32 s18, s18, 0xb79f000
	s_addc_u32 s19, s19, 0
	s_add_u32 s20, s18, 0x10000
	s_addc_u32 s21, s19, 0
	s_add_u32 s22, s20, 0x10000
	s_addc_u32 s23, s21, 0
	s_add_u32 s24, s22, 0x10000
	s_addc_u32 s25, s23, 0
	s_lshl_b32 s38, s47, 11
	s_add_u32 s26, s14, s38
	s_addc_u32 s27, s15, 0
	s_add_u32 s26, s26, 0x10a0000
	s_addc_u32 s27, s27, 0
	s_add_u32 s28, s26, 0x10000
	s_addc_u32 s29, s27, 0
	s_add_u32 s30, s28, 0x10000
	s_addc_u32 s31, s29, 0
	s_add_u32 s34, s30, 0x10000
	s_addc_u32 s35, s31, 0
	v_mov_b32_e32 v254, v64
	s_mov_b32 s39, 1
	s_waitcnt vmcnt(8)
	s_barrier
	ds_read_b128 v[70:73], v156
	ds_read_b128 v[74:77], v157 offset:16384
	ds_read_b128 v[78:81], v157 offset:20480
	ds_read_b128 v[82:85], v157 offset:24576
	ds_read_b128 v[86:89], v157 offset:28672
	ds_read_b128 v[90:93], v158
	ds_read_b128 v[94:97], v159 offset:16384
	ds_read_b128 v[98:101], v159 offset:20480
	ds_read_b128 v[102:105], v159 offset:24576
	ds_read_b128 v[106:109], v159 offset:28672
	ds_read_b128 v[110:113], v160
	ds_read_b128 v[202:205], v161 offset:16384
	ds_read_b128 v[206:209], v161 offset:20480
	ds_read_b128 v[210:213], v161 offset:24576
	ds_read_b128 v[214:217], v161 offset:28672
	ds_read_b128 v[218:221], v162
	ds_read_b128 v[222:225], v163 offset:16384
	ds_read_b128 v[226:229], v163 offset:20480
	ds_read_b128 v[230:233], v163 offset:24576
	ds_read_b128 v[234:237], v163 offset:28672
	s_waitcnt lgkmcnt(0)
	s_barrier
	s_mov_b32 m0, s36
	s_setprio 1
	v_mfma_f32_32x32x16_bf16 v[48:63], v[70:73], v[74:77], v[48:63]
	v_mfma_f32_32x32x16_bf16 v[32:47], v[70:73], v[78:81], v[32:47]
	global_load_lds_dwordx4 v254, s[18:19]
	s_add_u32 m0, m0, 0x1000
	v_mfma_f32_32x32x16_bf16 v[16:31], v[70:73], v[82:85], v[16:31]
	v_mfma_f32_32x32x16_bf16 v[0:15], v[70:73], v[86:89], v[0:15]
	global_load_lds_dwordx4 v254, s[20:21]
	s_add_u32 m0, m0, 0x1000
	v_mfma_f32_32x32x16_bf16 v[48:63], v[90:93], v[94:97], v[48:63]
	v_mfma_f32_32x32x16_bf16 v[32:47], v[90:93], v[98:101], v[32:47]
	global_load_lds_dwordx4 v254, s[22:23]
	s_add_u32 m0, m0, 0x1000
	v_mfma_f32_32x32x16_bf16 v[16:31], v[90:93], v[102:105], v[16:31]
	v_mfma_f32_32x32x16_bf16 v[0:15], v[90:93], v[106:109], v[0:15]
	global_load_lds_dwordx4 v254, s[24:25]
	s_add_u32 m0, m0, 0x1000
	v_mfma_f32_32x32x16_bf16 v[48:63], v[110:113], v[202:205], v[48:63]
	v_mfma_f32_32x32x16_bf16 v[32:47], v[110:113], v[206:209], v[32:47]
	global_load_lds_dwordx4 v254, s[26:27]
	s_add_u32 m0, m0, 0x1000
	v_mfma_f32_32x32x16_bf16 v[16:31], v[110:113], v[210:213], v[16:31]
	v_mfma_f32_32x32x16_bf16 v[0:15], v[110:113], v[214:217], v[0:15]
	global_load_lds_dwordx4 v254, s[28:29]
	s_add_u32 m0, m0, 0x1000
	v_mfma_f32_32x32x16_bf16 v[48:63], v[218:221], v[222:225], v[48:63]
	v_mfma_f32_32x32x16_bf16 v[32:47], v[218:221], v[226:229], v[32:47]
	global_load_lds_dwordx4 v254, s[30:31]
	s_add_u32 m0, m0, 0x1000
	v_mfma_f32_32x32x16_bf16 v[16:31], v[218:221], v[230:233], v[16:31]
	v_mfma_f32_32x32x16_bf16 v[0:15], v[218:221], v[234:237], v[0:15]
	global_load_lds_dwordx4 v254, s[34:35]
	s_setprio 0
	v_add_u32_e32 v254, 0x80, v254
	s_waitcnt vmcnt(8)
	s_barrier
	ds_read_b128 v[70:73], v156 offset:32768
	ds_read_b128 v[74:77], v157 offset:49152
	ds_read_b128 v[78:81], v157 offset:53248
	ds_read_b128 v[82:85], v157 offset:57344
	ds_read_b128 v[86:89], v157 offset:61440
	ds_read_b128 v[90:93], v158 offset:32768
	ds_read_b128 v[94:97], v159 offset:49152
	ds_read_b128 v[98:101], v159 offset:53248
	ds_read_b128 v[102:105], v159 offset:57344
	ds_read_b128 v[106:109], v159 offset:61440
	ds_read_b128 v[110:113], v160 offset:32768
	ds_read_b128 v[202:205], v161 offset:49152
	ds_read_b128 v[206:209], v161 offset:53248
	ds_read_b128 v[210:213], v161 offset:57344
	ds_read_b128 v[214:217], v161 offset:61440
	ds_read_b128 v[218:221], v162 offset:32768
	ds_read_b128 v[222:225], v163 offset:49152
	ds_read_b128 v[226:229], v163 offset:53248
	ds_read_b128 v[230:233], v163 offset:57344
	ds_read_b128 v[234:237], v163 offset:61440
	s_waitcnt lgkmcnt(0)
	s_barrier
	s_add_u32 m0, s36, 0x8000
	s_setprio 1
	v_mfma_f32_32x32x16_bf16 v[48:63], v[70:73], v[74:77], v[48:63]
	v_mfma_f32_32x32x16_bf16 v[32:47], v[70:73], v[78:81], v[32:47]
	global_load_lds_dwordx4 v254, s[18:19]
	s_add_u32 m0, m0, 0x1000
	v_mfma_f32_32x32x16_bf16 v[16:31], v[70:73], v[82:85], v[16:31]
	v_mfma_f32_32x32x16_bf16 v[0:15], v[70:73], v[86:89], v[0:15]
	global_load_lds_dwordx4 v254, s[20:21]
	s_add_u32 m0, m0, 0x1000
	v_mfma_f32_32x32x16_bf16 v[48:63], v[90:93], v[94:97], v[48:63]
	v_mfma_f32_32x32x16_bf16 v[32:47], v[90:93], v[98:101], v[32:47]
	global_load_lds_dwordx4 v254, s[22:23]
	s_add_u32 m0, m0, 0x1000
	v_mfma_f32_32x32x16_bf16 v[16:31], v[90:93], v[102:105], v[16:31]
	v_mfma_f32_32x32x16_bf16 v[0:15], v[90:93], v[106:109], v[0:15]
	global_load_lds_dwordx4 v254, s[24:25]
	s_add_u32 m0, m0, 0x1000
	v_mfma_f32_32x32x16_bf16 v[48:63], v[110:113], v[202:205], v[48:63]
	v_mfma_f32_32x32x16_bf16 v[32:47], v[110:113], v[206:209], v[32:47]
	global_load_lds_dwordx4 v254, s[26:27]
	s_add_u32 m0, m0, 0x1000
	v_mfma_f32_32x32x16_bf16 v[16:31], v[110:113], v[210:213], v[16:31]
	v_mfma_f32_32x32x16_bf16 v[0:15], v[110:113], v[214:217], v[0:15]
	global_load_lds_dwordx4 v254, s[28:29]
	s_add_u32 m0, m0, 0x1000
	v_mfma_f32_32x32x16_bf16 v[48:63], v[218:221], v[222:225], v[48:63]
	v_mfma_f32_32x32x16_bf16 v[32:47], v[218:221], v[226:229], v[32:47]
	global_load_lds_dwordx4 v254, s[30:31]
	s_add_u32 m0, m0, 0x1000
	v_mfma_f32_32x32x16_bf16 v[16:31], v[218:221], v[230:233], v[16:31]
	v_mfma_f32_32x32x16_bf16 v[0:15], v[218:221], v[234:237], v[0:15]
	global_load_lds_dwordx4 v254, s[34:35]
	s_setprio 0
	v_add_u32_e32 v254, 0x80, v254
	s_branch .LBB0_1326

.LBB0_1326:
	s_add_i32 s58, s66, 0xffffe000
	s_lshr_b32 s58, s58, 12
	s_mulk_i32 s58, 0x1800
	v_mov_b32_e32 v70, s70
	s_add_i32 s58, s58, 0xa800
	ds_read_b64 v[70:71], v70
	s_cmp_gt_i32 s6, 63
	s_cselect_b32 s6, s58, 0x9000
	s_lshl_b64 s[58:59], s[6:7], 2
	s_add_u32 s6, s14, s58
	s_addc_u32 s65, s15, s59
	s_waitcnt lgkmcnt(0)
	v_readfirstlane_b32 s58, v70
	v_readfirstlane_b32 s59, v71
	s_add_u32 s60, s58, 0x2000
	s_addc_u32 s61, s59, 0
	s_lshl_b32 s58, s64, 14
	s_add_i32 s58, s58, 0xa0000
	s_ashr_i32 s59, s58, 31
	s_lshl_b64 s[58:59], s[58:59], 2
	s_add_u32 s58, s10, s58
	s_addc_u32 s59, s11, s59
	s_add_u32 s62, s6, 0x5ba2000
	v_or_b32_e32 v102, s68, v138
	v_add_u32_e32 v70, s66, v139
	s_addc_u32 s63, s65, 0
	v_lshlrev_b32_e32 v188, 10, v70
	v_ashrrev_i32_e32 v103, 31, v102
	s_add_u32 s64, s6, 0x5ba4000
	v_lshlrev_b64 v[72:73], 2, v[102:103]
	v_or_b32_e32 v186, 0x400, v188
	v_or_b32_e32 v185, 0x4400, v188
	v_or_b32_e32 v189, 0x4c00, v188
	v_or_b32_e32 v193, 0x6c00, v188
	s_addc_u32 s65, s65, 0
	v_lshl_add_u64 v[74:75], s[62:63], 0, v[72:73]
	v_add_u32_e32 v132, v188, v102
	v_add_u32_e32 v134, v186, v102
	v_or_b32_e32 v184, 0x800, v188
	v_or_b32_e32 v183, 0xc00, v188
	v_or_b32_e32 v181, 0x2000, v188
	v_or_b32_e32 v179, 0x2400, v188
	v_or_b32_e32 v71, 0x2800, v188
	v_or_b32_e32 v180, 0x2c00, v188
	v_or_b32_e32 v182, 0x4000, v188
	v_add_u32_e32 v112, v185, v102
	v_or_b32_e32 v187, 0x4800, v188
	v_add_u32_e32 v118, v189, v102
	v_or_b32_e32 v190, 0x6000, v188
	v_or_b32_e32 v191, 0x6400, v188
	v_or_b32_e32 v192, 0x6800, v188
	v_add_u32_e32 v128, v193, v102
	global_load_dword v194, v[74:75], off
	v_lshl_add_u64 v[74:75], s[60:61], 0, v[72:73]
	v_lshl_add_u64 v[72:73], s[64:65], 0, v[72:73]
	v_ashrrev_i32_e32 v135, 31, v134
	v_add_u32_e32 v136, v184, v102
	v_add_u32_e32 v130, v183, v102
	v_add_u32_e32 v122, v181, v102
	v_add_u32_e32 v114, v179, v102
	v_add_u32_e32 v106, v71, v102
	v_add_u32_e32 v108, v180, v102
	v_add_u32_e32 v110, v182, v102
	v_ashrrev_i32_e32 v113, 31, v112
	v_add_u32_e32 v116, v187, v102
	v_ashrrev_i32_e32 v119, 31, v118
	v_add_u32_e32 v120, v190, v102
	v_add_u32_e32 v124, v191, v102
	v_add_u32_e32 v126, v192, v102
	v_ashrrev_i32_e32 v129, 31, v128
	v_ashrrev_i32_e32 v133, 31, v132
	global_load_dword v196, v[72:73], off
	v_lshl_add_u64 v[88:89], v[134:135], 2, s[12:13]
	v_ashrrev_i32_e32 v137, 31, v136
	v_ashrrev_i32_e32 v131, 31, v130
	v_ashrrev_i32_e32 v123, 31, v122
	v_ashrrev_i32_e32 v115, 31, v114
	v_ashrrev_i32_e32 v107, 31, v106
	v_ashrrev_i32_e32 v109, 31, v108
	v_ashrrev_i32_e32 v111, 31, v110
	v_lshl_add_u64 v[86:87], v[112:113], 2, s[12:13]
	v_ashrrev_i32_e32 v117, 31, v116
	v_lshl_add_u64 v[92:93], v[118:119], 2, s[12:13]
	v_ashrrev_i32_e32 v121, 31, v120
	v_ashrrev_i32_e32 v125, 31, v124
	v_ashrrev_i32_e32 v127, 31, v126
	v_lshl_add_u64 v[100:101], v[128:129], 2, s[12:13]
	v_lshl_add_u64 v[104:105], v[132:133], 2, s[12:13]
	global_load_dword v195, v[74:75], off
	v_lshl_add_u64 v[84:85], v[136:137], 2, s[12:13]
	v_lshl_add_u64 v[82:83], v[130:131], 2, s[12:13]
	v_lshl_add_u64 v[78:79], v[122:123], 2, s[12:13]
	v_lshl_add_u64 v[72:73], v[114:115], 2, s[12:13]
	v_lshl_add_u64 v[74:75], v[106:107], 2, s[12:13]
	v_lshl_add_u64 v[76:77], v[108:109], 2, s[12:13]
	v_lshl_add_u64 v[80:81], v[110:111], 2, s[12:13]
	global_load_dword v178, v[88:89], off
	global_load_dword v177, v[84:85], off
	global_load_dword v176, v[82:83], off
	global_load_dword v175, v[78:79], off
	global_load_dword v174, v[72:73], off
	global_load_dword v173, v[74:75], off
	global_load_dword v172, v[76:77], off
	global_load_dword v171, v[80:81], off
	v_lshl_add_u64 v[90:91], v[116:117], 2, s[12:13]
	global_load_dword v170, v[86:87], off
	global_load_dword v168, v[90:91], off
	v_lshl_add_u64 v[94:95], v[120:121], 2, s[12:13]
	v_lshl_add_u64 v[96:97], v[124:125], 2, s[12:13]
	v_lshl_add_u64 v[98:99], v[126:127], 2, s[12:13]
	global_load_dword v169, v[92:93], off
	global_load_dword v167, v[94:95], off
	global_load_dword v166, v[96:97], off
	global_load_dword v165, v[98:99], off
	global_load_dword v103, v[100:101], off
	global_load_dword v197, v[104:105], off
	v_lshl_add_u64 v[106:107], v[106:107], 1, s[8:9]
	s_waitcnt vmcnt(0)
	v_add_f32_e32 v196, 1.0, v196
	v_mul_f32_e32 v195, v195, v196
	v_fmac_f32_e32 v178, v49, v194
	v_fmac_f32_e32 v177, v50, v194
	v_fmac_f32_e32 v176, v51, v194
	v_fmac_f32_e32 v175, v52, v194
	v_fmac_f32_e32 v174, v53, v194
	v_fmac_f32_e32 v173, v54, v194
	v_fmac_f32_e32 v172, v55, v194
	v_fmac_f32_e32 v171, v56, v194
	v_fmac_f32_e32 v170, v57, v194
	v_fmac_f32_e32 v168, v58, v194
	v_fmac_f32_e32 v169, v59, v194
	v_fmac_f32_e32 v167, v60, v194
	v_fmac_f32_e32 v166, v61, v194
	v_fmac_f32_e32 v165, v62, v194
	v_fmac_f32_e32 v103, v63, v194
	v_fmac_f32_e32 v197, v48, v194
	v_mul_f32_e32 v48, v195, v197
	v_cvt_pk_bf16_f32 v58, v48, s0
	v_or_b32_e32 v48, 32, v102
	v_ashrrev_i32_e32 v49, 31, v48
	v_lshlrev_b64 v[52:53], 2, v[48:49]
	global_store_dword v[88:89], v178, off sc1
	global_store_dword v[84:85], v177, off sc1
	global_store_dword v[82:83], v176, off sc1
	global_store_dword v[78:79], v175, off sc1
	global_store_dword v[72:73], v174, off sc1
	global_store_dword v[74:75], v173, off sc1
	global_store_dword v[76:77], v172, off sc1
	global_store_dword v[80:81], v171, off sc1
	global_store_dword v[86:87], v170, off sc1
	global_store_dword v[90:91], v168, off sc1
	global_store_dword v[92:93], v169, off sc1
	global_store_dword v[94:95], v167, off sc1
	global_store_dword v[96:97], v166, off sc1
	global_store_dword v[98:99], v165, off sc1
	global_store_dword v[100:101], v103, off sc1
	global_store_dword v[104:105], v197, off sc1
	v_lshl_add_u64 v[50:51], v[132:133], 1, s[8:9]
	v_lshl_add_u64 v[56:57], s[64:65], 0, v[52:53]
	global_load_dword v196, v[104:105], off offset:128
	v_lshl_add_u64 v[54:55], s[60:61], 0, v[52:53]
	global_load_dword v132, v[56:57], off
	global_load_dword v133, v[54:55], off
	v_mul_f32_e32 v49, v195, v178
	global_store_short v[50:51], v58, off sc1
	v_lshl_add_u64 v[50:51], s[62:63], 0, v[52:53]
	global_load_dword v194, v[50:51], off
	v_cvt_pk_bf16_f32 v49, v49, s0
	v_lshl_add_u64 v[50:51], v[134:135], 1, s[8:9]
	global_store_short v[50:51], v49, off sc1
	v_mul_f32_e32 v49, v195, v177
	v_cvt_pk_bf16_f32 v49, v49, s0
	v_lshl_add_u64 v[50:51], v[136:137], 1, s[8:9]
	global_store_short v[50:51], v49, off sc1
	v_mul_f32_e32 v49, v195, v176
	v_cvt_pk_bf16_f32 v49, v49, s0
	v_lshl_add_u64 v[50:51], v[130:131], 1, s[8:9]
	global_store_short v[50:51], v49, off sc1
	v_mul_f32_e32 v49, v195, v175
	v_cvt_pk_bf16_f32 v49, v49, s0
	v_lshl_add_u64 v[50:51], v[122:123], 1, s[8:9]
	global_store_short v[50:51], v49, off sc1
	v_mul_f32_e32 v49, v195, v174
	v_cvt_pk_bf16_f32 v49, v49, s0
	v_lshl_add_u64 v[50:51], v[114:115], 1, s[8:9]
	global_store_short v[50:51], v49, off sc1
	v_mul_f32_e32 v49, v195, v173
	global_load_dword v62, v[84:85], off offset:128
	global_load_dword v60, v[78:79], off offset:128
	global_load_dword v59, v[72:73], off offset:128
	global_load_dword v58, v[74:75], off offset:128
	global_load_dword v56, v[80:81], off offset:128
	global_load_dword v57, v[76:77], off offset:128
	global_load_dword v55, v[86:87], off offset:128
	global_load_dword v61, v[82:83], off offset:128
	global_load_dword v54, v[90:91], off offset:128
	global_load_dword v53, v[92:93], off offset:128
	global_load_dword v52, v[94:95], off offset:128
	global_load_dword v51, v[96:97], off offset:128
	global_load_dword v50, v[98:99], off offset:128
	v_cvt_pk_bf16_f32 v63, v49, s0
	global_load_dword v49, v[100:101], off offset:128
	s_waitcnt vmcnt(19)
	v_fmac_f32_e32 v196, v32, v194
	global_store_short v[106:107], v63, off sc1
	global_load_dword v63, v[88:89], off offset:128
	v_mul_f32_e32 v106, v195, v172
	v_cvt_pk_bf16_f32 v114, v106, s0
	v_lshl_add_u64 v[106:107], v[108:109], 1, s[8:9]
	global_store_short v[106:107], v114, off sc1
	v_mul_f32_e32 v106, v195, v171
	v_cvt_pk_bf16_f32 v108, v106, s0
	v_lshl_add_u64 v[106:107], v[110:111], 1, s[8:9]
	global_store_short v[106:107], v108, off sc1
	v_mul_f32_e32 v106, v195, v170
	v_cvt_pk_bf16_f32 v108, v106, s0
	v_lshl_add_u64 v[106:107], v[112:113], 1, s[8:9]
	global_store_short v[106:107], v108, off sc1
	v_mul_f32_e32 v106, v195, v168
	v_cvt_pk_bf16_f32 v108, v106, s0
	v_lshl_add_u64 v[106:107], v[116:117], 1, s[8:9]
	global_store_short v[106:107], v108, off sc1
	v_mul_f32_e32 v106, v195, v169
	v_cvt_pk_bf16_f32 v108, v106, s0
	v_lshl_add_u64 v[106:107], v[118:119], 1, s[8:9]
	global_store_short v[106:107], v108, off sc1
	v_mul_f32_e32 v106, v195, v167
	v_cvt_pk_bf16_f32 v108, v106, s0
	v_lshl_add_u64 v[106:107], v[120:121], 1, s[8:9]
	global_store_short v[106:107], v108, off sc1
	v_mul_f32_e32 v106, v195, v166
	v_cvt_pk_bf16_f32 v108, v106, s0
	v_lshl_add_u64 v[106:107], v[124:125], 1, s[8:9]
	global_store_short v[106:107], v108, off sc1
	v_mul_f32_e32 v106, v195, v165
	v_cvt_pk_bf16_f32 v108, v106, s0
	v_lshl_add_u64 v[106:107], v[126:127], 1, s[8:9]
	global_store_short v[106:107], v108, off sc1
	v_mul_f32_e32 v106, v195, v103
	v_cvt_pk_bf16_f32 v108, v106, s0
	v_lshl_add_u64 v[106:107], v[128:129], 1, s[8:9]
	global_store_short v[106:107], v108, off sc1
	v_add_f32_e32 v106, 1.0, v132
	v_mul_f32_e32 v110, v133, v106
	v_add_u32_e32 v106, v188, v48
	s_waitcnt vmcnt(24)
	v_fmac_f32_e32 v62, v34, v194
	s_waitcnt vmcnt(17)
	v_fmac_f32_e32 v61, v35, v194
	v_fmac_f32_e32 v60, v36, v194
	v_fmac_f32_e32 v59, v37, v194
	v_fmac_f32_e32 v58, v38, v194
	v_fmac_f32_e32 v57, v39, v194
	v_fmac_f32_e32 v56, v40, v194
	v_fmac_f32_e32 v55, v41, v194
	s_waitcnt vmcnt(16)
	v_fmac_f32_e32 v54, v42, v194
	s_waitcnt vmcnt(15)
	v_fmac_f32_e32 v53, v43, v194
	s_waitcnt vmcnt(14)
	v_fmac_f32_e32 v52, v44, v194
	s_waitcnt vmcnt(13)
	v_fmac_f32_e32 v51, v45, v194
	s_waitcnt vmcnt(12)
	v_fmac_f32_e32 v50, v46, v194
	s_waitcnt vmcnt(11)
	v_fmac_f32_e32 v49, v47, v194
	v_ashrrev_i32_e32 v107, 31, v106
	global_store_dword v[104:105], v196, off offset:128 sc1
	v_mul_f32_e32 v32, v110, v196
	global_store_dword v[84:85], v62, off offset:128 sc1
	global_store_dword v[82:83], v61, off offset:128 sc1
	global_store_dword v[78:79], v60, off offset:128 sc1
	global_store_dword v[72:73], v59, off offset:128 sc1
	global_store_dword v[74:75], v58, off offset:128 sc1
	global_store_dword v[76:77], v57, off offset:128 sc1
	global_store_dword v[80:81], v56, off offset:128 sc1
	global_store_dword v[86:87], v55, off offset:128 sc1
	global_store_dword v[90:91], v54, off offset:128 sc1
	global_store_dword v[92:93], v53, off offset:128 sc1
	global_store_dword v[94:95], v52, off offset:128 sc1
	global_store_dword v[96:97], v51, off offset:128 sc1
	global_store_dword v[98:99], v50, off offset:128 sc1
	global_store_dword v[100:101], v49, off offset:128 sc1
	v_cvt_pk_bf16_f32 v32, v32, s0
	v_lshl_add_u64 v[106:107], v[106:107], 1, s[8:9]
	v_add_u32_e32 v108, v186, v48
	global_load_dword v45, v[88:89], off offset:256
	v_ashrrev_i32_e32 v109, 31, v108
	global_store_short v[106:107], v32, off sc1
	v_mul_f32_e32 v113, v110, v56
	v_cvt_pk_bf16_f32 v113, v113, s0
	v_mul_f32_e32 v106, v196, v196
	s_waitcnt vmcnt(26)
	v_fmac_f32_e32 v63, v33, v194
	v_mul_f32_e32 v32, v110, v63
	v_cvt_pk_bf16_f32 v34, v32, s0
	v_lshl_add_u64 v[32:33], v[108:109], 1, s[8:9]
	global_store_short v[32:33], v34, off sc1
	v_add_u32_e32 v32, v184, v48
	v_ashrrev_i32_e32 v33, 31, v32
	v_mul_f32_e32 v34, v110, v62
	v_cvt_pk_bf16_f32 v34, v34, s0
	v_lshl_add_u64 v[32:33], v[32:33], 1, s[8:9]
	global_store_short v[32:33], v34, off sc1
	v_add_u32_e32 v32, v183, v48
	v_ashrrev_i32_e32 v33, 31, v32
	v_mul_f32_e32 v34, v110, v61
	v_cvt_pk_bf16_f32 v34, v34, s0
	v_lshl_add_u64 v[32:33], v[32:33], 1, s[8:9]
	global_store_short v[32:33], v34, off sc1
	v_add_u32_e32 v32, v181, v48
	v_ashrrev_i32_e32 v33, 31, v32
	v_mul_f32_e32 v34, v110, v60
	v_cvt_pk_bf16_f32 v34, v34, s0
	v_lshl_add_u64 v[32:33], v[32:33], 1, s[8:9]
	global_store_short v[32:33], v34, off sc1
	v_add_u32_e32 v32, v179, v48
	v_ashrrev_i32_e32 v33, 31, v32
	v_mul_f32_e32 v34, v110, v59
	v_cvt_pk_bf16_f32 v42, v34, s0
	v_lshl_add_u64 v[34:35], v[32:33], 1, s[8:9]
	v_or_b32_e32 v32, 64, v102
	v_ashrrev_i32_e32 v33, 31, v32
	v_lshlrev_b64 v[36:37], 2, v[32:33]
	global_store_dword v[88:89], v63, off offset:128 sc1
	v_lshl_add_u64 v[40:41], s[64:65], 0, v[36:37]
	v_lshl_add_u64 v[38:39], s[60:61], 0, v[36:37]
	global_load_dword v107, v[40:41], off
	global_load_dword v111, v[38:39], off
	v_mul_f32_e32 v33, v110, v58
	global_store_short v[34:35], v42, off sc1
	v_lshl_add_u64 v[34:35], s[62:63], 0, v[36:37]
	global_load_dword v112, v[34:35], off
	v_add_u32_e32 v34, v71, v48
	v_ashrrev_i32_e32 v35, 31, v34
	v_cvt_pk_bf16_f32 v33, v33, s0
	v_lshl_add_u64 v[34:35], v[34:35], 1, s[8:9]
	global_store_short v[34:35], v33, off sc1
	v_add_u32_e32 v34, v180, v48
	v_ashrrev_i32_e32 v35, 31, v34
	v_mul_f32_e32 v33, v110, v57
	v_cvt_pk_bf16_f32 v33, v33, s0
	v_lshl_add_u64 v[34:35], v[34:35], 1, s[8:9]
	global_load_dword v38, v[90:91], off offset:256
	global_load_dword v37, v[92:93], off offset:256
	global_load_dword v36, v[94:95], off offset:256
	global_load_dword v114, v[104:105], off offset:256
	global_load_dword v47, v[84:85], off offset:256
	global_load_dword v39, v[86:87], off offset:256
	global_load_dword v46, v[82:83], off offset:256
	global_load_dword v44, v[78:79], off offset:256
	global_load_dword v43, v[72:73], off offset:256
	global_load_dword v42, v[74:75], off offset:256
	global_load_dword v40, v[80:81], off offset:256
	global_load_dword v41, v[76:77], off offset:256
	v_add_u32_e32 v108, v182, v48
	global_store_short v[34:35], v33, off sc1
	global_load_dword v35, v[96:97], off offset:256
	v_ashrrev_i32_e32 v109, 31, v108
	global_load_dword v34, v[98:99], off offset:256
	global_load_dword v33, v[100:101], off offset:256
	v_lshl_add_u64 v[108:109], v[108:109], 1, s[8:9]
	global_store_short v[108:109], v113, off sc1
	v_add_u32_e32 v108, v185, v48
	v_ashrrev_i32_e32 v109, 31, v108
	v_mul_f32_e32 v113, v110, v55
	v_cvt_pk_bf16_f32 v113, v113, s0
	v_lshl_add_u64 v[108:109], v[108:109], 1, s[8:9]
	global_store_short v[108:109], v113, off sc1
	v_add_u32_e32 v108, v187, v48
	v_ashrrev_i32_e32 v109, 31, v108
	v_mul_f32_e32 v113, v110, v54
	v_cvt_pk_bf16_f32 v113, v113, s0
	v_lshl_add_u64 v[108:109], v[108:109], 1, s[8:9]
	global_store_short v[108:109], v113, off sc1
	v_add_u32_e32 v108, v189, v48
	v_ashrrev_i32_e32 v109, 31, v108
	v_mul_f32_e32 v113, v110, v53
	v_cvt_pk_bf16_f32 v113, v113, s0
	v_lshl_add_u64 v[108:109], v[108:109], 1, s[8:9]
	global_store_short v[108:109], v113, off sc1
	v_add_u32_e32 v108, v190, v48
	v_ashrrev_i32_e32 v109, 31, v108
	v_mul_f32_e32 v113, v110, v52
	v_cvt_pk_bf16_f32 v113, v113, s0
	v_lshl_add_u64 v[108:109], v[108:109], 1, s[8:9]
	global_store_short v[108:109], v113, off sc1
	v_add_u32_e32 v108, v191, v48
	v_ashrrev_i32_e32 v109, 31, v108
	v_mul_f32_e32 v113, v110, v51
	v_cvt_pk_bf16_f32 v113, v113, s0
	v_lshl_add_u64 v[108:109], v[108:109], 1, s[8:9]
	global_store_short v[108:109], v113, off sc1
	v_add_u32_e32 v108, v192, v48
	v_ashrrev_i32_e32 v109, 31, v108
	v_mul_f32_e32 v113, v110, v50
	v_cvt_pk_bf16_f32 v113, v113, s0
	v_lshl_add_u64 v[108:109], v[108:109], 1, s[8:9]
	global_store_short v[108:109], v113, off sc1
	v_add_u32_e32 v108, v193, v48
	v_ashrrev_i32_e32 v109, 31, v108
	v_mul_f32_e32 v48, v110, v49
	v_cvt_pk_bf16_f32 v48, v48, s0
	v_lshl_add_u64 v[108:109], v[108:109], 1, s[8:9]
	global_store_short v[108:109], v48, off sc1
	v_add_u32_e32 v108, v188, v32
	v_ashrrev_i32_e32 v109, 31, v108
	s_waitcnt vmcnt(28)
	v_add_f32_e32 v48, 1.0, v107
	s_waitcnt vmcnt(27)
	v_mul_f32_e32 v48, v111, v48
	v_fmac_f32_e32 v106, v197, v197
	s_waitcnt vmcnt(25)
	v_fmac_f32_e32 v45, v17, v112
	global_store_dword v[88:89], v45, off offset:256 sc1
	s_waitcnt vmcnt(24)
	v_fmac_f32_e32 v38, v26, v112
	s_waitcnt vmcnt(23)
	v_fmac_f32_e32 v37, v27, v112
	s_waitcnt vmcnt(22)
	v_fmac_f32_e32 v36, v28, v112
	s_waitcnt vmcnt(21)
	v_fmac_f32_e32 v114, v16, v112
	v_mul_f32_e32 v16, v48, v114
	s_waitcnt vmcnt(20)
	v_fmac_f32_e32 v47, v18, v112
	v_cvt_pk_bf16_f32 v18, v16, s0
	v_lshl_add_u64 v[16:17], v[108:109], 1, s[8:9]
	global_store_short v[16:17], v18, off sc1
	v_add_u32_e32 v16, v186, v32
	v_ashrrev_i32_e32 v17, 31, v16
	v_mul_f32_e32 v18, v48, v45
	v_cvt_pk_bf16_f32 v18, v18, s0
	v_lshl_add_u64 v[16:17], v[16:17], 1, s[8:9]
	global_store_short v[16:17], v18, off sc1
	v_add_u32_e32 v16, v184, v32
	v_ashrrev_i32_e32 v17, 31, v16
	v_mul_f32_e32 v18, v48, v47
	v_cvt_pk_bf16_f32 v18, v18, s0
	v_lshl_add_u64 v[16:17], v[16:17], 1, s[8:9]
	s_waitcnt vmcnt(20)
	v_fmac_f32_e32 v46, v19, v112
	global_store_short v[16:17], v18, off sc1
	v_add_u32_e32 v16, v183, v32
	v_ashrrev_i32_e32 v17, 31, v16
	v_mul_f32_e32 v18, v48, v46
	s_waitcnt vmcnt(20)
	v_fmac_f32_e32 v44, v20, v112
	v_cvt_pk_bf16_f32 v18, v18, s0
	v_lshl_add_u64 v[16:17], v[16:17], 1, s[8:9]
	global_store_short v[16:17], v18, off sc1
	v_mul_f32_e32 v16, v48, v44
	v_cvt_pk_bf16_f32 v26, v16, s0
	v_or_b32_e32 v16, 0x60, v102
	v_add_u32_e32 v18, v181, v32
	v_ashrrev_i32_e32 v17, 31, v16
	s_waitcnt vmcnt(20)
	v_fmac_f32_e32 v43, v21, v112
	s_waitcnt vmcnt(19)
	v_fmac_f32_e32 v42, v22, v112
	s_waitcnt vmcnt(17)
	v_fmac_f32_e32 v41, v23, v112
	v_fmac_f32_e32 v40, v24, v112
	v_fmac_f32_e32 v39, v25, v112
	s_waitcnt vmcnt(15)
	v_fmac_f32_e32 v35, v29, v112
	s_waitcnt vmcnt(14)
	v_fmac_f32_e32 v34, v30, v112
	s_waitcnt vmcnt(13)
	v_fmac_f32_e32 v33, v31, v112
	v_ashrrev_i32_e32 v19, 31, v18
	v_lshlrev_b64 v[20:21], 2, v[16:17]
	global_store_dword v[84:85], v47, off offset:256 sc1
	global_store_dword v[82:83], v46, off offset:256 sc1
	global_store_dword v[78:79], v44, off offset:256 sc1
	global_store_dword v[72:73], v43, off offset:256 sc1
	global_store_dword v[74:75], v42, off offset:256 sc1
	global_store_dword v[76:77], v41, off offset:256 sc1
	global_store_dword v[80:81], v40, off offset:256 sc1
	global_store_dword v[86:87], v39, off offset:256 sc1
	global_store_dword v[90:91], v38, off offset:256 sc1
	global_store_dword v[92:93], v37, off offset:256 sc1
	global_store_dword v[94:95], v36, off offset:256 sc1
	global_store_dword v[96:97], v35, off offset:256 sc1
	global_store_dword v[98:99], v34, off offset:256 sc1
	global_store_dword v[100:101], v33, off offset:256 sc1
	global_store_dword v[104:105], v114, off offset:256 sc1
	v_lshl_add_u64 v[24:25], s[64:65], 0, v[20:21]
	v_lshl_add_u64 v[18:19], v[18:19], 1, s[8:9]
	global_load_dword v29, v[104:105], off offset:384
	v_lshl_add_u64 v[22:23], s[60:61], 0, v[20:21]
	global_load_dword v17, v[24:25], off
	global_load_dword v30, v[22:23], off
	global_load_dword v28, v[88:89], off offset:384
	global_load_dword v27, v[84:85], off offset:384
	v_fmac_f32_e32 v106, v114, v114
	global_store_short v[18:19], v26, off sc1
	v_lshl_add_u64 v[18:19], s[62:63], 0, v[20:21]
	global_load_dword v102, v[18:19], off
	v_add_u32_e32 v18, v179, v32
	v_ashrrev_i32_e32 v19, 31, v18
	v_mul_f32_e32 v20, v48, v43
	v_cvt_pk_bf16_f32 v20, v20, s0
	v_lshl_add_u64 v[18:19], v[18:19], 1, s[8:9]
	global_store_short v[18:19], v20, off sc1
	v_add_u32_e32 v18, v71, v32
	v_ashrrev_i32_e32 v19, 31, v18
	v_mul_f32_e32 v20, v48, v42
	v_cvt_pk_bf16_f32 v20, v20, s0
	v_lshl_add_u64 v[18:19], v[18:19], 1, s[8:9]
	global_store_short v[18:19], v20, off sc1
	v_add_u32_e32 v18, v180, v32
	v_ashrrev_i32_e32 v19, 31, v18
	v_mul_f32_e32 v20, v48, v41
	v_cvt_pk_bf16_f32 v20, v20, s0
	v_lshl_add_u64 v[18:19], v[18:19], 1, s[8:9]
	global_store_short v[18:19], v20, off sc1
	v_add_u32_e32 v18, v182, v32
	v_ashrrev_i32_e32 v19, 31, v18
	v_mul_f32_e32 v20, v48, v40
	v_cvt_pk_bf16_f32 v20, v20, s0
	v_lshl_add_u64 v[18:19], v[18:19], 1, s[8:9]
	global_store_short v[18:19], v20, off sc1
	v_add_u32_e32 v18, v185, v32
	v_ashrrev_i32_e32 v19, 31, v18
	v_mul_f32_e32 v20, v48, v39
	v_cvt_pk_bf16_f32 v20, v20, s0
	v_lshl_add_u64 v[18:19], v[18:19], 1, s[8:9]
	global_store_short v[18:19], v20, off sc1
	v_add_u32_e32 v18, v187, v32
	v_ashrrev_i32_e32 v19, 31, v18
	v_mul_f32_e32 v20, v48, v38
	v_cvt_pk_bf16_f32 v20, v20, s0
	v_lshl_add_u64 v[18:19], v[18:19], 1, s[8:9]
	global_store_short v[18:19], v20, off sc1
	v_add_u32_e32 v18, v189, v32
	v_ashrrev_i32_e32 v19, 31, v18
	v_mul_f32_e32 v20, v48, v37
	v_cvt_pk_bf16_f32 v20, v20, s0
	v_lshl_add_u64 v[18:19], v[18:19], 1, s[8:9]
	global_store_short v[18:19], v20, off sc1
	v_add_u32_e32 v18, v190, v32
	v_ashrrev_i32_e32 v19, 31, v18
	v_mul_f32_e32 v20, v48, v36
	v_cvt_pk_bf16_f32 v20, v20, s0
	v_lshl_add_u64 v[18:19], v[18:19], 1, s[8:9]
	global_store_short v[18:19], v20, off sc1
	v_add_u32_e32 v18, v191, v32
	v_ashrrev_i32_e32 v19, 31, v18
	v_mul_f32_e32 v20, v48, v35
	v_cvt_pk_bf16_f32 v20, v20, s0
	v_lshl_add_u64 v[18:19], v[18:19], 1, s[8:9]
	global_store_short v[18:19], v20, off sc1
	v_add_u32_e32 v18, v192, v32
	v_ashrrev_i32_e32 v19, 31, v18
	v_mul_f32_e32 v20, v48, v34
	v_cvt_pk_bf16_f32 v20, v20, s0
	v_lshl_add_u64 v[18:19], v[18:19], 1, s[8:9]
	global_store_short v[18:19], v20, off sc1
	v_add_u32_e32 v18, v193, v32
	v_ashrrev_i32_e32 v19, 31, v18
	v_mul_f32_e32 v20, v48, v33
	v_cvt_pk_bf16_f32 v20, v20, s0
	v_lshl_add_u64 v[18:19], v[18:19], 1, s[8:9]
	global_store_short v[18:19], v20, off sc1
	global_load_dword v20, v[86:87], off offset:384
	v_add_u32_e32 v18, v188, v16
	global_load_dword v26, v[82:83], off offset:384
	global_load_dword v25, v[78:79], off offset:384
	global_load_dword v24, v[72:73], off offset:384
	global_load_dword v23, v[74:75], off offset:384
	global_load_dword v21, v[80:81], off offset:384
	global_load_dword v22, v[76:77], off offset:384
	s_waitcnt vmcnt(23)
	v_add_f32_e32 v17, 1.0, v17
	s_waitcnt vmcnt(22)
	v_mul_f32_e32 v32, v30, v17
	v_ashrrev_i32_e32 v19, 31, v18
	v_lshl_add_u64 v[18:19], v[18:19], 1, s[8:9]
	v_add_u32_e32 v30, v186, v16
	s_waitcnt vmcnt(18)
	v_fmac_f32_e32 v29, v0, v102
	v_mul_f32_e32 v0, v32, v29
	v_cvt_pk_bf16_f32 v0, v0, s0
	global_store_short v[18:19], v0, off sc1
	global_load_dword v19, v[90:91], off offset:384
	v_ashrrev_i32_e32 v31, 31, v30
	global_load_dword v18, v[92:93], off offset:384
	v_fmac_f32_e32 v28, v1, v102
	v_mul_f32_e32 v0, v32, v28
	v_cvt_pk_bf16_f32 v17, v0, s0
	v_lshl_add_u64 v[0:1], v[30:31], 1, s[8:9]
	global_store_short v[0:1], v17, off sc1
	v_add_u32_e32 v0, v184, v16
	v_fmac_f32_e32 v27, v2, v102
	global_load_dword v17, v[94:95], off offset:384
	v_ashrrev_i32_e32 v1, 31, v0
	v_mul_f32_e32 v2, v32, v27
	v_cvt_pk_bf16_f32 v2, v2, s0
	v_lshl_add_u64 v[0:1], v[0:1], 1, s[8:9]
	global_store_short v[0:1], v2, off sc1
	v_add_u32_e32 v0, v183, v16
	global_load_dword v2, v[96:97], off offset:384
	v_ashrrev_i32_e32 v1, 31, v0
	v_lshl_add_u64 v[0:1], v[0:1], 1, s[8:9]
	v_add_u32_e32 v30, v181, v16
	v_ashrrev_i32_e32 v31, 31, v30
	v_lshl_add_u64 v[30:31], v[30:31], 1, s[8:9]
	v_fmac_f32_e32 v106, v29, v29
	global_store_dword v[104:105], v29, off offset:384 sc1
	global_store_dword v[88:89], v28, off offset:384 sc1
	global_store_dword v[84:85], v27, off offset:384 sc1
	s_waitcnt vmcnt(16)
	v_fmac_f32_e32 v20, v9, v102
	global_store_dword v[86:87], v20, off offset:384 sc1
	s_waitcnt vmcnt(16)
	v_fmac_f32_e32 v26, v3, v102
	v_mul_f32_e32 v3, v32, v26
	v_cvt_pk_bf16_f32 v3, v3, s0
	global_store_short v[0:1], v3, off sc1
	global_load_dword v1, v[98:99], off offset:384
	s_waitcnt vmcnt(17)
	v_fmac_f32_e32 v25, v4, v102
	v_mul_f32_e32 v0, v32, v25
	v_cvt_pk_bf16_f32 v0, v0, s0
	global_store_short v[30:31], v0, off sc1
	global_load_dword v0, v[100:101], off offset:384
	v_add_u32_e32 v30, v179, v16
	s_waitcnt vmcnt(18)
	v_fmac_f32_e32 v24, v5, v102
	v_ashrrev_i32_e32 v31, 31, v30
	v_mul_f32_e32 v3, v32, v24
	v_cvt_pk_bf16_f32 v3, v3, s0
	v_lshl_add_u64 v[4:5], v[30:31], 1, s[8:9]
	global_store_short v[4:5], v3, off sc1
	v_add_u32_e32 v4, v71, v16
	s_waitcnt vmcnt(18)
	v_fmac_f32_e32 v23, v6, v102
	v_ashrrev_i32_e32 v5, 31, v4
	v_mul_f32_e32 v3, v32, v23
	v_cvt_pk_bf16_f32 v3, v3, s0
	v_lshl_add_u64 v[4:5], v[4:5], 1, s[8:9]
	global_store_short v[4:5], v3, off sc1
	v_add_u32_e32 v4, v180, v16
	s_waitcnt vmcnt(17)
	v_fmac_f32_e32 v22, v7, v102
	v_ashrrev_i32_e32 v5, 31, v4
	v_mul_f32_e32 v3, v32, v22
	v_cvt_pk_bf16_f32 v3, v3, s0
	v_lshl_add_u64 v[4:5], v[4:5], 1, s[8:9]
	global_store_short v[4:5], v3, off sc1
	v_add_u32_e32 v4, v182, v16
	v_fmac_f32_e32 v21, v8, v102
	v_ashrrev_i32_e32 v5, 31, v4
	v_mul_f32_e32 v3, v32, v21
	v_cvt_pk_bf16_f32 v3, v3, s0
	v_lshl_add_u64 v[4:5], v[4:5], 1, s[8:9]
	global_store_short v[4:5], v3, off sc1
	v_add_u32_e32 v4, v185, v16
	v_ashrrev_i32_e32 v5, 31, v4
	v_mul_f32_e32 v3, v32, v20
	v_cvt_pk_bf16_f32 v3, v3, s0
	v_lshl_add_u64 v[4:5], v[4:5], 1, s[8:9]
	global_store_short v[4:5], v3, off sc1
	v_add_u32_e32 v4, v187, v16
	s_waitcnt vmcnt(18)
	v_fmac_f32_e32 v19, v10, v102
	v_ashrrev_i32_e32 v5, 31, v4
	v_mul_f32_e32 v3, v32, v19
	v_cvt_pk_bf16_f32 v3, v3, s0
	v_lshl_add_u64 v[4:5], v[4:5], 1, s[8:9]
	global_store_short v[4:5], v3, off sc1
	v_add_u32_e32 v4, v189, v16
	s_waitcnt vmcnt(18)
	v_fmac_f32_e32 v18, v11, v102
	v_ashrrev_i32_e32 v5, 31, v4
	v_mul_f32_e32 v3, v32, v18
	v_cvt_pk_bf16_f32 v3, v3, s0
	v_lshl_add_u64 v[4:5], v[4:5], 1, s[8:9]
	global_store_short v[4:5], v3, off sc1
	v_add_u32_e32 v4, v190, v16
	s_waitcnt vmcnt(17)
	v_fmac_f32_e32 v17, v12, v102
	v_ashrrev_i32_e32 v5, 31, v4
	v_mul_f32_e32 v3, v32, v17
	v_cvt_pk_bf16_f32 v3, v3, s0
	v_lshl_add_u64 v[4:5], v[4:5], 1, s[8:9]
	global_store_short v[4:5], v3, off sc1
	v_add_u32_e32 v4, v191, v16
	s_waitcnt vmcnt(16)
	v_fmac_f32_e32 v2, v13, v102
	v_ashrrev_i32_e32 v5, 31, v4
	v_mul_f32_e32 v3, v32, v2
	v_cvt_pk_bf16_f32 v3, v3, s0
	v_lshl_add_u64 v[4:5], v[4:5], 1, s[8:9]
	global_store_short v[4:5], v3, off sc1
	v_add_u32_e32 v4, v192, v16
	v_ashrrev_i32_e32 v5, 31, v4
	v_lshl_add_u64 v[4:5], v[4:5], 1, s[8:9]
	v_xor_b32_e32 v13, 16, v164
	v_add_u32_e32 v10, v193, v16
	v_ashrrev_i32_e32 v11, 31, v10
	v_lshl_add_u64 v[10:11], v[10:11], 1, s[8:9]
	v_ashrrev_i32_e32 v71, 31, v70
	global_store_dword v[82:83], v26, off offset:384 sc1
	global_store_dword v[78:79], v25, off offset:384 sc1
	global_store_dword v[72:73], v24, off offset:384 sc1
	global_store_dword v[74:75], v23, off offset:384 sc1
	s_waitcnt vmcnt(15)
	v_fmac_f32_e32 v1, v14, v102
	v_mul_f32_e32 v3, v32, v1
	v_cvt_pk_bf16_f32 v3, v3, s0
	global_store_short v[4:5], v3, off sc1
	v_and_b32_e32 v4, 64, v164
	v_xor_b32_e32 v3, 1, v164
	v_add_u32_e32 v7, 64, v4
	v_cmp_lt_i32_e32 vcc, v3, v7
	v_xor_b32_e32 v4, 2, v164
	s_waitcnt vmcnt(14)
	v_fmac_f32_e32 v0, v15, v102
	v_cndmask_b32_e32 v3, v164, v3, vcc
	v_lshlrev_b32_e32 v3, 2, v3
	ds_bpermute_b32 v5, v3, v106
	v_cmp_lt_i32_e32 vcc, v4, v7
	v_mul_f32_e32 v12, v32, v0
	v_cvt_pk_bf16_f32 v12, v12, s0
	v_cndmask_b32_e32 v4, v164, v4, vcc
	v_lshlrev_b32_e32 v4, 2, v4
	s_waitcnt lgkmcnt(0)
	v_add_f32_e32 v6, v106, v5
	ds_bpermute_b32 v8, v4, v6
	v_xor_b32_e32 v5, 4, v164
	v_cmp_lt_i32_e32 vcc, v5, v7
	global_store_dword v[76:77], v22, off offset:384 sc1
	global_store_dword v[80:81], v21, off offset:384 sc1
	v_cndmask_b32_e32 v5, v164, v5, vcc
	v_lshlrev_b32_e32 v5, 2, v5
	s_waitcnt lgkmcnt(0)
	v_add_f32_e32 v8, v6, v8
	ds_bpermute_b32 v9, v5, v8
	v_xor_b32_e32 v6, 8, v164
	v_cmp_lt_i32_e32 vcc, v6, v7
	global_store_dword v[90:91], v19, off offset:384 sc1
	global_store_dword v[92:93], v18, off offset:384 sc1
	v_cndmask_b32_e32 v6, v164, v6, vcc
	v_lshlrev_b32_e32 v6, 2, v6
	s_waitcnt lgkmcnt(0)
	v_add_f32_e32 v8, v8, v9
	ds_bpermute_b32 v9, v6, v8
	v_cmp_lt_i32_e32 vcc, v13, v7
	global_store_dword v[94:95], v17, off offset:384 sc1
	global_store_dword v[96:97], v2, off offset:384 sc1
	v_cndmask_b32_e32 v7, v164, v13, vcc
	v_lshlrev_b32_e32 v7, 2, v7
	s_waitcnt lgkmcnt(0)
	v_add_f32_e32 v8, v8, v9
	ds_bpermute_b32 v9, v7, v8
	global_store_dword v[98:99], v1, off offset:384 sc1
	global_store_dword v[100:101], v0, off offset:384 sc1
	global_store_short v[10:11], v12, off sc1
	s_and_saveexec_b64 s[60:61], s[0:1]
	s_cbranch_execz .LBB0_1328
	s_waitcnt lgkmcnt(0)
	v_add_f32_e32 v10, v8, v9
	v_lshl_add_u64 v[8:9], v[70:71], 2, s[58:59]
	global_store_dword v[8:9], v10, off sc1

.LBB0_1358:
	s_cmp_gt_i32 s17, 17
	s_cselect_b64 s[6:7], -1, 0
	s_and_b64 s[0:1], s[4:5], s[6:7]
	s_andn2_b64 vcc, exec, s[0:1]
	s_cbranch_vccnz .LBB0_1370
	s_waitcnt vmcnt(0)
	v_or_b32_e32 v0, v201, v200
	s_movk_i32 s0, 0x3ff
	v_and_or_b32 v0, v0, s0, v199
	v_cmp_eq_u32_e32 vcc, 0, v0
	s_waitcnt lgkmcnt(0)
	s_barrier
	s_and_saveexec_b64 s[0:1], vcc
	s_cbranch_execz .LBB0_1369
	s_add_u32 s4, s14, 0x5be8c00
	s_addc_u32 s5, s15, 0
	s_lshl_b32 s3, s2, 1
	v_mov_b32_e32 v0, s3
	v_mov_b32_e32 v1, 0x9311
	global_store_short v0, v1, s[4:5] sc1
	s_cmp_lg_u32 s2, 0
	s_cbranch_scc1 .Lgbar_wait_16
	s_lshr_b32 s3, s33, 3
	s_bfm_b64 s[8:9], s3, 0
	s_cmpk_gt_u32 s33, 0x1ff
	s_cselect_b64 s[8:9], -1, s[8:9]
	s_mov_b64 exec, -1
	v_mbcnt_lo_u32_b32 v229, -1, 0
	v_mbcnt_hi_u32_b32 v229, -1, v229
	v_lshlrev_b32_e32 v229, 4, v229
	s_mov_b32 s10, 0x93119311
	s_mov_b64 exec, s[8:9]

.LBB0_1370:
	s_cmp_lt_i32 s16, 18
	s_cselect_b64 s[0:1], -1, 0
	s_and_b64 s[4:5], s[0:1], s[6:7]
	s_andn2_b64 vcc, exec, s[4:5]
	s_cbranch_vccnz .LBB0_1378
	s_ashr_i32 s3, s2, 31
	s_and_b32 s3, s3, s33
	s_add_i32 s3, s3, s2
	s_cmpk_gt_i32 s3, 0x15ff
	s_cbranch_scc1 .LBB0_1378
	v_lshrrev_b32_e32 v0, 3, v199
	s_waitcnt lgkmcnt(0)
	v_lshrrev_b32_e32 v1, 5, v199
	v_bfe_u32 v4, v199, 1, 3
	v_lshlrev_b32_e32 v5, 4, v199
	v_bfe_u32 v2, v199, 5, 1
	v_xor_b32_e32 v6, v5, v199
	v_lshlrev_b32_e32 v7, 11, v0
	s_movk_i32 s4, 0x70
	v_bitop3_b32 v1, v1, v4, 1 bitop3:0x6c
	v_and_or_b32 v76, v6, s4, v7
	v_lshlrev_b32_e32 v7, 4, v1
	v_bitop3_b32 v1, v2, v4, 2 bitop3:0x36
	v_lshrrev_b32_e32 v3, 1, v199
	v_lshlrev_b32_e32 v9, 4, v1
	v_bitop3_b32 v1, v2, v4, 4 bitop3:0x36
	v_mov_b32_e32 v77, 0
	v_and_b32_e32 v3, 0x1e0, v3
	v_lshlrev_b32_e32 v10, 4, v1
	v_bitop3_b32 v1, v2, v4, 6 bitop3:0x36
	v_lshlrev_b32_e32 v2, 4, v1
	v_and_or_b32 v93, v0, 4, v3
	v_lshl_add_u64 v[0:1], s[14:15], 0, v[76:77]
	s_mov_b64 s[6:7], 0x679f000
	v_lshl_add_u64 v[78:79], v[0:1], 0, s[6:7]
	s_mov_b64 s[6:7], 0x2fa0000
	v_lshl_add_u64 v[80:81], v[0:1], 0, s[6:7]
	s_add_u32 s6, s14, 0x5ece000
	s_addc_u32 s7, s15, 0
	v_and_b32_e32 v92, 31, v199
	s_add_u32 s10, s14, 0x5c2d000
	v_or_b32_e32 v6, v3, v92
	s_addc_u32 s11, s15, 0
	v_lshl_add_u32 v6, v6, 7, 0
	v_lshl_add_u32 v8, v92, 7, 0
	s_add_u32 s8, s14, 0x879f000
	v_add_u32_e32 v94, 0, v5
	s_mov_b32 s5, 0
	s_addc_u32 s9, s15, 0
	v_add_u32_e32 v95, 0x4000, v94
	s_mov_b64 s[18:19], 0x10000
	v_add_u32_e32 v96, 0x1000, v94
	v_add_u32_e32 v97, 0x5000, v94
	s_mov_b64 s[20:21], 0x20000
	v_add_u32_e32 v98, 0x2000, v94
	v_add_u32_e32 v99, 0x6000, v94
	s_mov_b64 s[22:23], 0x30000
	v_add_u32_e32 v100, 0x3000, v94
	v_add_u32_e32 v101, 0x7000, v94
	s_mov_b64 s[24:25], 0x679f080
	s_mov_b64 s[26:27], 0x2fa0080
	v_add_u32_e32 v102, 0x8000, v94
	v_add_u32_e32 v103, 0xc000, v94
	s_mov_b64 s[28:29], 0x67af080
	v_add_u32_e32 v104, 0x9000, v94
	s_mov_b64 s[30:31], 0x2fb0080
	v_add_u32_e32 v105, 0xd000, v94
	s_mov_b64 s[34:35], 0x67bf080
	v_add_u32_e32 v106, 0xa000, v94
	s_mov_b64 s[36:37], 0x2fc0080
	v_add_u32_e32 v107, 0xe000, v94
	s_mov_b64 s[38:39], 0x67cf080
	v_add_u32_e32 v108, 0xb000, v94
	s_mov_b64 s[40:41], 0x2fd0080
	v_add_u32_e32 v109, 0xf000, v94
	v_add_u32_e32 v110, v6, v7
	v_add_u32_e32 v111, v8, v7
	s_waitcnt vmcnt(5)
	v_add_u32_e32 v112, v6, v9
	v_add_u32_e32 v113, v8, v9
	v_add_u32_e32 v114, v6, v10
	v_add_u32_e32 v115, v8, v10
	s_waitcnt vmcnt(4)
	v_add_u32_e32 v116, v6, v2
	v_add_u32_e32 v117, v8, v2
	s_mov_b64 s[42:43], 0x679f100
	s_mov_b64 s[44:45], 0x2fa0100
	s_mov_b64 s[46:47], 0x67af100
	s_mov_b64 s[48:49], 0x2fb0100
	s_mov_b64 s[50:51], 0x67bf100
	s_mov_b64 s[52:53], 0x2fc0100
	s_mov_b64 s[54:55], 0x67cf100
	s_mov_b64 s[56:57], 0x2fd0100
	s_movk_i32 s68, 0x1600
	s_mov_b32 s69, 0x10000
	s_mov_b32 s70, 0x20000
	s_mov_b32 s71, 0x30000
	s_mov_b32 s72, 0x40000
	s_mov_b32 s73, 0x50000
	s_mov_b32 s74, 0x60000
	s_mov_b32 s75, 0x70000
	v_mov_b32_e32 v118, 0x358637bd
	s_mov_b32 s39, 0
	s_branch .LBB0_1374

.Lmap_done_2:
	s_lshl_b32 s60, s4, 7
	s_lshl_b32 s58, s76, 7
	s_ashr_i32 s61, s60, 31
	s_ashr_i32 s59, s58, 31
	s_lshl_b64 s[62:63], s[60:61], 11
	s_lshl_b64 s[64:65], s[58:59], 11
	s_cmp_eq_u32 s39, 1
	s_cbranch_scc1 .Lgk_pfhead_p17
	s_lshl_b32 s38, s60, 11
	s_add_u32 s18, s14, s38
	s_addc_u32 s19, s15, 0
	s_add_u32 s18, s18, 0x679f000
	s_addc_u32 s19, s19, 0
	s_add_u32 s20, s18, 0x10000
	s_addc_u32 s21, s19, 0
	s_add_u32 s22, s20, 0x10000
	s_addc_u32 s23, s21, 0
	s_add_u32 s24, s22, 0x10000
	s_addc_u32 s25, s23, 0
	s_lshl_b32 s38, s58, 11
	s_add_u32 s26, s14, s38
	s_addc_u32 s27, s15, 0
	s_add_u32 s26, s26, 0x2fa0000
	s_addc_u32 s27, s27, 0
	s_add_u32 s28, s26, 0x10000
	s_addc_u32 s29, s27, 0
	s_add_u32 s30, s28, 0x10000
	s_addc_u32 s31, s29, 0
	s_add_u32 s34, s30, 0x10000
	s_addc_u32 s35, s31, 0
	v_readfirstlane_b32 s36, v94
	v_mov_b32_e32 v254, v76
	s_mov_b32 m0, s36
	s_nop 0
	global_load_lds_dwordx4 v254, s[18:19]
	s_add_u32 m0, m0, 0x1000
	s_nop 0
	global_load_lds_dwordx4 v254, s[20:21]
	s_add_u32 m0, m0, 0x1000
	s_nop 0
	global_load_lds_dwordx4 v254, s[22:23]
	s_add_u32 m0, m0, 0x1000
	s_nop 0
	global_load_lds_dwordx4 v254, s[24:25]
	s_add_u32 m0, m0, 0x1000
	s_nop 0
	global_load_lds_dwordx4 v254, s[26:27]
	s_add_u32 m0, m0, 0x1000
	s_nop 0
	global_load_lds_dwordx4 v254, s[28:29]
	s_add_u32 m0, m0, 0x1000
	s_nop 0
	global_load_lds_dwordx4 v254, s[30:31]
	s_add_u32 m0, m0, 0x1000
	s_nop 0
	global_load_lds_dwordx4 v254, s[34:35]
	v_add_u32_e32 v254, 0x80, v254
	s_add_u32 m0, s36, 0x8000
	s_nop 0
	global_load_lds_dwordx4 v254, s[18:19]
	s_add_u32 m0, m0, 0x1000
	s_nop 0
	global_load_lds_dwordx4 v254, s[20:21]
	s_add_u32 m0, m0, 0x1000
	s_nop 0
	global_load_lds_dwordx4 v254, s[22:23]
	s_add_u32 m0, m0, 0x1000
	s_nop 0
	global_load_lds_dwordx4 v254, s[24:25]
	s_add_u32 m0, m0, 0x1000
	s_nop 0
	global_load_lds_dwordx4 v254, s[26:27]
	s_add_u32 m0, m0, 0x1000
	s_nop 0
	global_load_lds_dwordx4 v254, s[28:29]
	s_add_u32 m0, m0, 0x1000
	s_nop 0
	global_load_lds_dwordx4 v254, s[30:31]
	s_add_u32 m0, m0, 0x1000
	s_nop 0
	global_load_lds_dwordx4 v254, s[34:35]
	v_add_u32_e32 v254, 0x80, v254

.Lmap_done_2_pf_p17:
	s_lshl_b32 s44, s41, 7
	s_lshl_b32 s42, s50, 7
	s_ashr_i32 s45, s44, 31
	s_ashr_i32 s43, s42, 31
	s_lshl_b64 s[46:47], s[44:45], 11
	s_lshl_b64 s[48:49], s[42:43], 11
	s_lshl_b32 s38, s44, 11
	s_add_u32 s18, s14, s38
	s_addc_u32 s19, s15, 0
	s_add_u32 s18, s18, 0x679f000
	s_addc_u32 s19, s19, 0
	s_add_u32 s20, s18, 0x10000
	s_addc_u32 s21, s19, 0
	s_add_u32 s22, s20, 0x10000
	s_addc_u32 s23, s21, 0
	s_add_u32 s24, s22, 0x10000
	s_addc_u32 s25, s23, 0
	s_lshl_b32 s38, s42, 11
	s_add_u32 s26, s14, s38
	s_addc_u32 s27, s15, 0
	s_add_u32 s26, s26, 0x2fa0000
	s_addc_u32 s27, s27, 0
	s_add_u32 s28, s26, 0x10000
	s_addc_u32 s29, s27, 0
	s_add_u32 s30, s28, 0x10000
	s_addc_u32 s31, s29, 0
	s_add_u32 s34, s30, 0x10000
	s_addc_u32 s35, s31, 0
	v_mov_b32_e32 v254, v76
	s_mov_b32 s39, 1
	s_waitcnt vmcnt(8)
	s_barrier
	ds_read_b128 v[64:67], v110
	ds_read_b128 v[68:71], v111 offset:16384
	ds_read_b128 v[72:75], v111 offset:20480
	ds_read_b128 v[82:85], v111 offset:24576
	ds_read_b128 v[86:89], v111 offset:28672
	ds_read_b128 v[120:123], v112
	ds_read_b128 v[124:127], v113 offset:16384
	ds_read_b128 v[128:131], v113 offset:20480
	ds_read_b128 v[132:135], v113 offset:24576
	ds_read_b128 v[136:139], v113 offset:28672
	ds_read_b128 v[140:143], v114
	ds_read_b128 v[218:221], v115 offset:16384
	ds_read_b128 v[222:225], v115 offset:20480
	ds_read_b128 v[226:229], v115 offset:24576
	ds_read_b128 v[230:233], v115 offset:28672
	ds_read_b128 v[234:237], v116
	ds_read_b128 v[238:241], v117 offset:16384
	ds_read_b128 v[242:245], v117 offset:20480
	ds_read_b128 v[246:249], v117 offset:24576
	ds_read_b128 v[250:253], v117 offset:28672
	s_waitcnt lgkmcnt(0)
	s_barrier
	s_mov_b32 m0, s36
	s_setprio 1
	v_mfma_f32_32x32x16_bf16 v[48:63], v[64:67], v[68:71], v[48:63]
	v_mfma_f32_32x32x16_bf16 v[32:47], v[64:67], v[72:75], v[32:47]
	global_load_lds_dwordx4 v254, s[18:19]
	s_add_u32 m0, m0, 0x1000
	v_mfma_f32_32x32x16_bf16 v[16:31], v[64:67], v[82:85], v[16:31]
	v_mfma_f32_32x32x16_bf16 v[0:15], v[64:67], v[86:89], v[0:15]
	global_load_lds_dwordx4 v254, s[20:21]
	s_add_u32 m0, m0, 0x1000
	v_mfma_f32_32x32x16_bf16 v[48:63], v[120:123], v[124:127], v[48:63]
	v_mfma_f32_32x32x16_bf16 v[32:47], v[120:123], v[128:131], v[32:47]
	global_load_lds_dwordx4 v254, s[22:23]
	s_add_u32 m0, m0, 0x1000
	v_mfma_f32_32x32x16_bf16 v[16:31], v[120:123], v[132:135], v[16:31]
	v_mfma_f32_32x32x16_bf16 v[0:15], v[120:123], v[136:139], v[0:15]
	global_load_lds_dwordx4 v254, s[24:25]
	s_add_u32 m0, m0, 0x1000
	v_mfma_f32_32x32x16_bf16 v[48:63], v[140:143], v[218:221], v[48:63]
	v_mfma_f32_32x32x16_bf16 v[32:47], v[140:143], v[222:225], v[32:47]
	global_load_lds_dwordx4 v254, s[26:27]
	s_add_u32 m0, m0, 0x1000
	v_mfma_f32_32x32x16_bf16 v[16:31], v[140:143], v[226:229], v[16:31]
	v_mfma_f32_32x32x16_bf16 v[0:15], v[140:143], v[230:233], v[0:15]
	global_load_lds_dwordx4 v254, s[28:29]
	s_add_u32 m0, m0, 0x1000
	v_mfma_f32_32x32x16_bf16 v[48:63], v[234:237], v[238:241], v[48:63]
	v_mfma_f32_32x32x16_bf16 v[32:47], v[234:237], v[242:245], v[32:47]
	global_load_lds_dwordx4 v254, s[30:31]
	s_add_u32 m0, m0, 0x1000
	v_mfma_f32_32x32x16_bf16 v[16:31], v[234:237], v[246:249], v[16:31]
	v_mfma_f32_32x32x16_bf16 v[0:15], v[234:237], v[250:253], v[0:15]
	global_load_lds_dwordx4 v254, s[34:35]
	s_setprio 0
	v_add_u32_e32 v254, 0x80, v254
	s_waitcnt vmcnt(8)
	s_barrier
	ds_read_b128 v[64:67], v110 offset:32768
	ds_read_b128 v[68:71], v111 offset:49152
	ds_read_b128 v[72:75], v111 offset:53248
	ds_read_b128 v[82:85], v111 offset:57344
	ds_read_b128 v[86:89], v111 offset:61440
	ds_read_b128 v[120:123], v112 offset:32768
	ds_read_b128 v[124:127], v113 offset:49152
	ds_read_b128 v[128:131], v113 offset:53248
	ds_read_b128 v[132:135], v113 offset:57344
	ds_read_b128 v[136:139], v113 offset:61440
	ds_read_b128 v[140:143], v114 offset:32768
	ds_read_b128 v[218:221], v115 offset:49152
	ds_read_b128 v[222:225], v115 offset:53248
	ds_read_b128 v[226:229], v115 offset:57344
	ds_read_b128 v[230:233], v115 offset:61440
	ds_read_b128 v[234:237], v116 offset:32768
	ds_read_b128 v[238:241], v117 offset:49152
	ds_read_b128 v[242:245], v117 offset:53248
	ds_read_b128 v[246:249], v117 offset:57344
	ds_read_b128 v[250:253], v117 offset:61440
	s_waitcnt lgkmcnt(0)
	s_barrier
	s_add_u32 m0, s36, 0x8000
	s_setprio 1
	v_mfma_f32_32x32x16_bf16 v[48:63], v[64:67], v[68:71], v[48:63]
	v_mfma_f32_32x32x16_bf16 v[32:47], v[64:67], v[72:75], v[32:47]
	global_load_lds_dwordx4 v254, s[18:19]
	s_add_u32 m0, m0, 0x1000
	v_mfma_f32_32x32x16_bf16 v[16:31], v[64:67], v[82:85], v[16:31]
	v_mfma_f32_32x32x16_bf16 v[0:15], v[64:67], v[86:89], v[0:15]
	global_load_lds_dwordx4 v254, s[20:21]
	s_add_u32 m0, m0, 0x1000
	v_mfma_f32_32x32x16_bf16 v[48:63], v[120:123], v[124:127], v[48:63]
	v_mfma_f32_32x32x16_bf16 v[32:47], v[120:123], v[128:131], v[32:47]
	global_load_lds_dwordx4 v254, s[22:23]
	s_add_u32 m0, m0, 0x1000
	v_mfma_f32_32x32x16_bf16 v[16:31], v[120:123], v[132:135], v[16:31]
	v_mfma_f32_32x32x16_bf16 v[0:15], v[120:123], v[136:139], v[0:15]
	global_load_lds_dwordx4 v254, s[24:25]
	s_add_u32 m0, m0, 0x1000
	v_mfma_f32_32x32x16_bf16 v[48:63], v[140:143], v[218:221], v[48:63]
	v_mfma_f32_32x32x16_bf16 v[32:47], v[140:143], v[222:225], v[32:47]
	global_load_lds_dwordx4 v254, s[26:27]
	s_add_u32 m0, m0, 0x1000
	v_mfma_f32_32x32x16_bf16 v[16:31], v[140:143], v[226:229], v[16:31]
	v_mfma_f32_32x32x16_bf16 v[0:15], v[140:143], v[230:233], v[0:15]
	global_load_lds_dwordx4 v254, s[28:29]
	s_add_u32 m0, m0, 0x1000
	v_mfma_f32_32x32x16_bf16 v[48:63], v[234:237], v[238:241], v[48:63]
	v_mfma_f32_32x32x16_bf16 v[32:47], v[234:237], v[242:245], v[32:47]
	global_load_lds_dwordx4 v254, s[30:31]
	s_add_u32 m0, m0, 0x1000
	v_mfma_f32_32x32x16_bf16 v[16:31], v[234:237], v[246:249], v[16:31]
	v_mfma_f32_32x32x16_bf16 v[0:15], v[234:237], v[250:253], v[0:15]
	global_load_lds_dwordx4 v254, s[34:35]
	s_setprio 0
	v_add_u32_e32 v254, 0x80, v254
	s_branch .LBB0_1373

.LBB0_1378:
	s_cmp_gt_i32 s17, 18
	s_cselect_b64 s[6:7], -1, 0
	s_and_b64 s[0:1], s[0:1], s[6:7]
	s_andn2_b64 vcc, exec, s[0:1]
	s_cbranch_vccnz .LBB0_1390
	s_waitcnt vmcnt(0)
	v_or_b32_e32 v0, v201, v200
	s_movk_i32 s0, 0x3ff
	v_and_or_b32 v0, v0, s0, v199
	v_cmp_eq_u32_e32 vcc, 0, v0
	s_waitcnt lgkmcnt(0)
	s_barrier
	s_and_saveexec_b64 s[0:1], vcc
	s_cbranch_execz .LBB0_1389
	s_add_u32 s4, s14, 0x5be8c00
	s_addc_u32 s5, s15, 0
	s_lshl_b32 s3, s2, 1
	v_mov_b32_e32 v0, s3
	v_mov_b32_e32 v1, 0x9312
	global_store_short v0, v1, s[4:5] sc1
	s_cmp_lg_u32 s2, 0
	s_cbranch_scc1 .Lgbar_wait_17
	s_lshr_b32 s3, s33, 3
	s_bfm_b64 s[8:9], s3, 0
	s_cmpk_gt_u32 s33, 0x1ff
	s_cselect_b64 s[8:9], -1, s[8:9]
	s_mov_b64 exec, -1
	v_mbcnt_lo_u32_b32 v229, -1, 0
	v_mbcnt_hi_u32_b32 v229, -1, v229
	v_lshlrev_b32_e32 v229, 4, v229
	s_mov_b32 s10, 0x93129312
	s_mov_b64 exec, s[8:9]

.LBB0_1390:
	s_cmp_lt_i32 s16, 19
	s_cselect_b64 s[4:5], -1, 0
	s_and_b64 s[0:1], s[4:5], s[6:7]
	s_andn2_b64 vcc, exec, s[0:1]
	s_cbranch_vccnz .LBB0_1430
	s_ashr_i32 s0, s2, 31
	s_and_b32 s0, s0, s33
	s_add_i32 s3, s0, s2
	s_cmpk_gt_i32 s3, 0x3ff
	s_cbranch_scc1 .LBB0_1430
	s_waitcnt lgkmcnt(0)
	v_lshrrev_b32_e32 v1, 5, v199
	v_bfe_u32 v5, v199, 1, 3
	v_lshrrev_b32_e32 v6, 4, v199
	v_lshrrev_b32_e32 v0, 3, v199
	v_bfe_u32 v2, v199, 5, 1
	v_xor_b32_e32 v7, v6, v199
	v_bitop3_b32 v1, v1, v5, 1 bitop3:0x6c
	v_mul_u32_u24_e32 v3, 0xb00, v0
	v_lshlrev_b32_e32 v7, 3, v7
	v_lshlrev_b32_e32 v9, 4, v1
	v_bitop3_b32 v1, v2, v5, 2 bitop3:0x36
	v_lshrrev_b32_e32 v4, 1, v199
	v_and_or_b32 v7, v7, 56, v3
	v_lshlrev_b32_e32 v11, 4, v1
	v_bitop3_b32 v1, v2, v5, 4 bitop3:0x36
	v_lshlrev_b32_e32 v64, 1, v7
	v_mov_b32_e32 v65, 0
	v_and_b32_e32 v4, 0x1e0, v4
	v_lshlrev_b32_e32 v12, 4, v1
	v_bitop3_b32 v1, v2, v5, 6 bitop3:0x36
	v_lshlrev_b32_e32 v2, 4, v1
	s_waitcnt vmcnt(25)
	v_and_or_b32 v139, v0, 4, v4
	v_lshl_add_u64 v[0:1], s[14:15], 0, v[64:65]
	s_mov_b64 s[8:9], 0x879f000
	v_and_b32_e32 v138, 31, v199
	v_lshl_add_u64 v[66:67], v[0:1], 0, s[8:9]
	s_mov_b64 s[8:9], 0x50a0000
	s_add_u32 s10, s14, 0x5c4e000
	v_lshlrev_b32_e32 v7, 4, v199
	v_or_b32_e32 v8, v4, v138
	v_lshl_add_u64 v[68:69], v[0:1], 0, s[8:9]
	s_addc_u32 s11, s15, 0
	v_bitop3_b32 v0, v6, 7, v199 bitop3:0x48
	v_lshlrev_b32_e32 v1, 1, v3
	v_lshl_add_u32 v8, v8, 7, 0
	v_lshl_add_u32 v10, v138, 7, 0
	s_add_u32 s8, s14, 0x679f000
	v_lshl_or_b32 v64, v0, 4, v1
	v_add_u32_e32 v141, 0, v7
	v_mbcnt_lo_u32_b32 v0, -1, 0
	s_mov_b32 s7, 0
	v_cmp_eq_u32_e64 s[0:1], 0, v138
	s_addc_u32 s9, s15, 0
	v_mov_b32_e32 v140, 0x1600
	v_add_u32_e32 v142, 0x4000, v141
	s_mov_b64 s[18:19], 0x2c000
	v_add_u32_e32 v143, 0x1000, v141
	s_waitcnt vmcnt(24)
	v_add_u32_e32 v144, 0x5000, v141
	s_mov_b64 s[20:21], 0x58000
	v_add_u32_e32 v145, 0x2000, v141
	v_add_u32_e32 v146, 0x6000, v141
	s_mov_b64 s[22:23], 0x84000
	v_add_u32_e32 v147, 0x3000, v141
	v_add_u32_e32 v148, 0x7000, v141
	s_mov_b64 s[24:25], 0x879f080
	s_mov_b64 s[26:27], 0x50a0080
	v_add_u32_e32 v149, 0x8000, v141
	v_add_u32_e32 v150, 0xc000, v141
	s_mov_b64 s[28:29], 0x87cb080
	v_add_u32_e32 v151, 0x9000, v141
	s_mov_b64 s[30:31], 0x50cc080
	s_waitcnt vmcnt(23)
	v_add_u32_e32 v152, 0xd000, v141
	s_mov_b64 s[34:35], 0x87f7080
	v_add_u32_e32 v153, 0xa000, v141
	s_mov_b64 s[36:37], 0x50f8080
	v_add_u32_e32 v154, 0xe000, v141
	s_mov_b64 s[38:39], 0x8823080
	v_add_u32_e32 v155, 0xb000, v141
	s_mov_b64 s[40:41], 0x5124080
	s_waitcnt vmcnt(22)
	v_add_u32_e32 v156, 0xf000, v141
	v_add_u32_e32 v157, v8, v9
	v_add_u32_e32 v158, v10, v9
	v_add_u32_e32 v159, v8, v11
	s_waitcnt vmcnt(21)
	v_add_u32_e32 v160, v10, v11
	v_add_u32_e32 v161, v8, v12
	v_add_u32_e32 v162, v10, v12
	v_add_u32_e32 v163, v8, v2
	s_waitcnt vmcnt(19)
	v_add_u32_e32 v164, v10, v2
	s_mov_b64 s[42:43], 0x879f100
	s_mov_b64 s[44:45], 0x50a0100
	s_mov_b64 s[46:47], 0x87cb100
	s_mov_b64 s[48:49], 0x50cc100
	s_mov_b64 s[50:51], 0x87f7100
	s_mov_b64 s[52:53], 0x50f8100
	s_mov_b64 s[54:55], 0x8823100
	s_mov_b64 s[56:57], 0x5124100
	s_add_i32 s66, 0, 0x12068
	v_mbcnt_hi_u32_b32 v165, -1, v0
	s_mov_b32 s39, 0
	s_branch .LBB0_1394

.LBB0_1394:
	s_ashr_i32 s6, s3, 31
	s_lshr_b32 s6, s6, 26
	s_add_i32 s6, s3, s6
	s_ashr_i32 s58, s6, 6
	s_andn2_b32 s6, s6, 63
	s_sub_i32 s6, s3, s6
	s_ashr_i32 s59, s6, 31
	s_lshr_b32 s59, s59, 29
	s_add_i32 s59, s6, s59
	s_ashr_i32 s64, s59, 3
	s_and_b32 s59, s59, -8
	s_lshl_b32 s58, s58, 3
	s_sub_i32 s6, s6, s59
	s_add_i32 s6, s6, s58
	s_lshl_b32 s67, s6, 7
	s_lshl_b32 s68, s64, 7
	s_waitcnt lgkmcnt(0)
	s_cmp_eq_u32 s39, 1
	s_cbranch_scc1 .Lgk_pfhead_p18
	s_mul_i32 s38, s6, 0xb0000
	s_add_u32 s18, s14, s38
	s_addc_u32 s19, s15, 0
	s_add_u32 s18, s18, 0x879f000
	s_addc_u32 s19, s19, 0
	s_add_u32 s20, s18, 0x2c000
	s_addc_u32 s21, s19, 0
	s_add_u32 s22, s20, 0x2c000
	s_addc_u32 s23, s21, 0
	s_add_u32 s24, s22, 0x2c000
	s_addc_u32 s25, s23, 0
	s_mul_i32 s38, s64, 0xb0000
	s_add_u32 s26, s14, s38
	s_addc_u32 s27, s15, 0
	s_add_u32 s26, s26, 0x50a0000
	s_addc_u32 s27, s27, 0
	s_add_u32 s28, s26, 0x2c000
	s_addc_u32 s29, s27, 0
	s_add_u32 s30, s28, 0x2c000
	s_addc_u32 s31, s29, 0
	s_add_u32 s34, s30, 0x2c000
	s_addc_u32 s35, s31, 0
	v_readfirstlane_b32 s36, v141
	v_mov_b32_e32 v254, v64
	s_mov_b32 m0, s36
	s_nop 0
	global_load_lds_dwordx4 v254, s[18:19]
	s_add_u32 m0, m0, 0x1000
	s_nop 0
	global_load_lds_dwordx4 v254, s[20:21]
	s_add_u32 m0, m0, 0x1000
	s_nop 0
	global_load_lds_dwordx4 v254, s[22:23]
	s_add_u32 m0, m0, 0x1000
	s_nop 0
	global_load_lds_dwordx4 v254, s[24:25]
	s_add_u32 m0, m0, 0x1000
	s_nop 0
	global_load_lds_dwordx4 v254, s[26:27]
	s_add_u32 m0, m0, 0x1000
	s_nop 0
	global_load_lds_dwordx4 v254, s[28:29]
	s_add_u32 m0, m0, 0x1000
	s_nop 0
	global_load_lds_dwordx4 v254, s[30:31]
	s_add_u32 m0, m0, 0x1000
	s_nop 0
	global_load_lds_dwordx4 v254, s[34:35]
	v_add_u32_e32 v254, 0x80, v254
	s_add_u32 m0, s36, 0x8000
	s_nop 0
	global_load_lds_dwordx4 v254, s[18:19]
	s_add_u32 m0, m0, 0x1000
	s_nop 0
	global_load_lds_dwordx4 v254, s[20:21]
	s_add_u32 m0, m0, 0x1000
	s_nop 0
	global_load_lds_dwordx4 v254, s[22:23]
	s_add_u32 m0, m0, 0x1000
	s_nop 0
	global_load_lds_dwordx4 v254, s[24:25]
	s_add_u32 m0, m0, 0x1000
	s_nop 0
	global_load_lds_dwordx4 v254, s[26:27]
	s_add_u32 m0, m0, 0x1000
	s_nop 0
	global_load_lds_dwordx4 v254, s[28:29]
	s_add_u32 m0, m0, 0x1000
	s_nop 0
	global_load_lds_dwordx4 v254, s[30:31]
	s_add_u32 m0, m0, 0x1000
	s_nop 0
	global_load_lds_dwordx4 v254, s[34:35]
	v_add_u32_e32 v254, 0x80, v254

.LBB0_1394_pf_p18:
	s_ashr_i32 s41, s40, 31
	s_lshr_b32 s41, s41, 26
	s_add_i32 s41, s40, s41
	s_ashr_i32 s42, s41, 6
	s_andn2_b32 s41, s41, 63
	s_sub_i32 s41, s40, s41
	s_ashr_i32 s43, s41, 31
	s_lshr_b32 s43, s43, 29
	s_add_i32 s43, s41, s43
	s_ashr_i32 s44, s43, 3
	s_and_b32 s43, s43, -8
	s_lshl_b32 s42, s42, 3
	s_sub_i32 s41, s41, s43
	s_add_i32 s41, s41, s42
	s_lshl_b32 s45, s41, 7
	s_lshl_b32 s46, s44, 7
	s_mul_i32 s38, s41, 0xb0000
	s_add_u32 s18, s14, s38
	s_addc_u32 s19, s15, 0
	s_add_u32 s18, s18, 0x879f000
	s_addc_u32 s19, s19, 0
	s_add_u32 s20, s18, 0x2c000
	s_addc_u32 s21, s19, 0
	s_add_u32 s22, s20, 0x2c000
	s_addc_u32 s23, s21, 0
	s_add_u32 s24, s22, 0x2c000
	s_addc_u32 s25, s23, 0
	s_mul_i32 s38, s44, 0xb0000
	s_add_u32 s26, s14, s38
	s_addc_u32 s27, s15, 0
	s_add_u32 s26, s26, 0x50a0000
	s_addc_u32 s27, s27, 0
	s_add_u32 s28, s26, 0x2c000
	s_addc_u32 s29, s27, 0
	s_add_u32 s30, s28, 0x2c000
	s_addc_u32 s31, s29, 0
	s_add_u32 s34, s30, 0x2c000
	s_addc_u32 s35, s31, 0
	v_mov_b32_e32 v254, v64
	s_mov_b32 s39, 1
	s_waitcnt vmcnt(8)
	s_barrier
	ds_read_b128 v[70:73], v157
	ds_read_b128 v[74:77], v158 offset:16384
	ds_read_b128 v[78:81], v158 offset:20480
	ds_read_b128 v[82:85], v158 offset:24576
	ds_read_b128 v[86:89], v158 offset:28672
	ds_read_b128 v[90:93], v159
	ds_read_b128 v[94:97], v160 offset:16384
	ds_read_b128 v[98:101], v160 offset:20480
	ds_read_b128 v[102:105], v160 offset:24576
	ds_read_b128 v[106:109], v160 offset:28672
	ds_read_b128 v[110:113], v161
	ds_read_b128 v[202:205], v162 offset:16384
	ds_read_b128 v[206:209], v162 offset:20480
	ds_read_b128 v[210:213], v162 offset:24576
	ds_read_b128 v[214:217], v162 offset:28672
	ds_read_b128 v[218:221], v163
	ds_read_b128 v[222:225], v164 offset:16384
	ds_read_b128 v[226:229], v164 offset:20480
	ds_read_b128 v[230:233], v164 offset:24576
	ds_read_b128 v[234:237], v164 offset:28672
	s_waitcnt lgkmcnt(0)
	s_barrier
	s_mov_b32 m0, s36
	s_setprio 1
	v_mfma_f32_32x32x16_bf16 v[48:63], v[70:73], v[74:77], v[48:63]
	v_mfma_f32_32x32x16_bf16 v[32:47], v[70:73], v[78:81], v[32:47]
	global_load_lds_dwordx4 v254, s[18:19]
	s_add_u32 m0, m0, 0x1000
	v_mfma_f32_32x32x16_bf16 v[16:31], v[70:73], v[82:85], v[16:31]
	v_mfma_f32_32x32x16_bf16 v[0:15], v[70:73], v[86:89], v[0:15]
	global_load_lds_dwordx4 v254, s[20:21]
	s_add_u32 m0, m0, 0x1000
	v_mfma_f32_32x32x16_bf16 v[48:63], v[90:93], v[94:97], v[48:63]
	v_mfma_f32_32x32x16_bf16 v[32:47], v[90:93], v[98:101], v[32:47]
	global_load_lds_dwordx4 v254, s[22:23]
	s_add_u32 m0, m0, 0x1000
	v_mfma_f32_32x32x16_bf16 v[16:31], v[90:93], v[102:105], v[16:31]
	v_mfma_f32_32x32x16_bf16 v[0:15], v[90:93], v[106:109], v[0:15]
	global_load_lds_dwordx4 v254, s[24:25]
	s_add_u32 m0, m0, 0x1000
	v_mfma_f32_32x32x16_bf16 v[48:63], v[110:113], v[202:205], v[48:63]
	v_mfma_f32_32x32x16_bf16 v[32:47], v[110:113], v[206:209], v[32:47]
	global_load_lds_dwordx4 v254, s[26:27]
	s_add_u32 m0, m0, 0x1000
	v_mfma_f32_32x32x16_bf16 v[16:31], v[110:113], v[210:213], v[16:31]
	v_mfma_f32_32x32x16_bf16 v[0:15], v[110:113], v[214:217], v[0:15]
	global_load_lds_dwordx4 v254, s[28:29]
	s_add_u32 m0, m0, 0x1000
	v_mfma_f32_32x32x16_bf16 v[48:63], v[218:221], v[222:225], v[48:63]
	v_mfma_f32_32x32x16_bf16 v[32:47], v[218:221], v[226:229], v[32:47]
	global_load_lds_dwordx4 v254, s[30:31]
	s_add_u32 m0, m0, 0x1000
	v_mfma_f32_32x32x16_bf16 v[16:31], v[218:221], v[230:233], v[16:31]
	v_mfma_f32_32x32x16_bf16 v[0:15], v[218:221], v[234:237], v[0:15]
	global_load_lds_dwordx4 v254, s[34:35]
	s_setprio 0
	v_add_u32_e32 v254, 0x80, v254
	s_waitcnt vmcnt(8)
	s_barrier
	ds_read_b128 v[70:73], v157 offset:32768
	ds_read_b128 v[74:77], v158 offset:49152
	ds_read_b128 v[78:81], v158 offset:53248
	ds_read_b128 v[82:85], v158 offset:57344
	ds_read_b128 v[86:89], v158 offset:61440
	ds_read_b128 v[90:93], v159 offset:32768
	ds_read_b128 v[94:97], v160 offset:49152
	ds_read_b128 v[98:101], v160 offset:53248
	ds_read_b128 v[102:105], v160 offset:57344
	ds_read_b128 v[106:109], v160 offset:61440
	ds_read_b128 v[110:113], v161 offset:32768
	ds_read_b128 v[202:205], v162 offset:49152
	ds_read_b128 v[206:209], v162 offset:53248
	ds_read_b128 v[210:213], v162 offset:57344
	ds_read_b128 v[214:217], v162 offset:61440
	ds_read_b128 v[218:221], v163 offset:32768
	ds_read_b128 v[222:225], v164 offset:49152
	ds_read_b128 v[226:229], v164 offset:53248
	ds_read_b128 v[230:233], v164 offset:57344
	ds_read_b128 v[234:237], v164 offset:61440
	s_waitcnt lgkmcnt(0)
	s_barrier
	s_add_u32 m0, s36, 0x8000
	s_setprio 1
	v_mfma_f32_32x32x16_bf16 v[48:63], v[70:73], v[74:77], v[48:63]
	v_mfma_f32_32x32x16_bf16 v[32:47], v[70:73], v[78:81], v[32:47]
	global_load_lds_dwordx4 v254, s[18:19]
	s_add_u32 m0, m0, 0x1000
	v_mfma_f32_32x32x16_bf16 v[16:31], v[70:73], v[82:85], v[16:31]
	v_mfma_f32_32x32x16_bf16 v[0:15], v[70:73], v[86:89], v[0:15]
	global_load_lds_dwordx4 v254, s[20:21]
	s_add_u32 m0, m0, 0x1000
	v_mfma_f32_32x32x16_bf16 v[48:63], v[90:93], v[94:97], v[48:63]
	v_mfma_f32_32x32x16_bf16 v[32:47], v[90:93], v[98:101], v[32:47]
	global_load_lds_dwordx4 v254, s[22:23]
	s_add_u32 m0, m0, 0x1000
	v_mfma_f32_32x32x16_bf16 v[16:31], v[90:93], v[102:105], v[16:31]
	v_mfma_f32_32x32x16_bf16 v[0:15], v[90:93], v[106:109], v[0:15]
	global_load_lds_dwordx4 v254, s[24:25]
	s_add_u32 m0, m0, 0x1000
	v_mfma_f32_32x32x16_bf16 v[48:63], v[110:113], v[202:205], v[48:63]
	v_mfma_f32_32x32x16_bf16 v[32:47], v[110:113], v[206:209], v[32:47]
	global_load_lds_dwordx4 v254, s[26:27]
	s_add_u32 m0, m0, 0x1000
	v_mfma_f32_32x32x16_bf16 v[16:31], v[110:113], v[210:213], v[16:31]
	v_mfma_f32_32x32x16_bf16 v[0:15], v[110:113], v[214:217], v[0:15]
	global_load_lds_dwordx4 v254, s[28:29]
	s_add_u32 m0, m0, 0x1000
	v_mfma_f32_32x32x16_bf16 v[48:63], v[218:221], v[222:225], v[48:63]
	v_mfma_f32_32x32x16_bf16 v[32:47], v[218:221], v[226:229], v[32:47]
	global_load_lds_dwordx4 v254, s[30:31]
	s_add_u32 m0, m0, 0x1000
	v_mfma_f32_32x32x16_bf16 v[16:31], v[218:221], v[230:233], v[16:31]
	v_mfma_f32_32x32x16_bf16 v[0:15], v[218:221], v[234:237], v[0:15]
	global_load_lds_dwordx4 v254, s[34:35]
	s_setprio 0
	v_add_u32_e32 v254, 0x80, v254
	s_branch .LBB0_1398

.LBB0_1398:
	s_add_i32 s58, s67, 0xffffe000
	s_lshr_b32 s58, s58, 12
	s_mulk_i32 s58, 0x1800
	s_addk_i32 s58, 0x1800
	s_cmp_gt_i32 s6, 63
	s_cselect_b32 s62, s58, 0
	s_add_i32 s6, s62, 0x9000
	s_lshl_b64 s[58:59], s[6:7], 2
	s_add_u32 s6, s14, s58
	s_addc_u32 s58, s15, s59
	s_add_u32 s60, s6, 0x5ba5000
	s_addc_u32 s61, s58, 0
	s_add_i32 s6, s62, 0xd800
	s_lshl_b64 s[58:59], s[6:7], 2
	v_mov_b32_e32 v70, s66
	s_add_u32 s6, s14, s58
	ds_read_b64 v[70:71], v70
	s_addc_u32 s69, s15, s59
	s_lshl_b32 s58, s64, 14
	s_add_i32 s58, s58, 0xc0000
	s_ashr_i32 s59, s58, 31
	s_lshl_b64 s[58:59], s[58:59], 2
	s_add_u32 s58, s10, s58
	s_waitcnt lgkmcnt(0)
	v_readfirstlane_b32 s63, v70
	s_addc_u32 s59, s11, s59
	v_or_b32_e32 v102, s68, v138
	v_add_u32_e32 v70, s67, v139
	v_readfirstlane_b32 s65, v71
	s_add_u32 s62, s63, 0x3000
	v_ashrrev_i32_e32 v103, 31, v102
	v_lshlrev_b32_e32 v191, 10, v70
	s_addc_u32 s63, s65, 0
	v_lshlrev_b64 v[72:73], 2, v[102:103]
	v_or_b32_e32 v187, 0x400, v191
	v_or_b32_e32 v186, 0x4400, v191
	v_or_b32_e32 v189, 0x4c00, v191
	v_or_b32_e32 v194, 0x6c00, v191
	s_add_u32 s64, s6, 0x5ba1000
	v_lshl_add_u64 v[74:75], s[60:61], 0, v[72:73]
	v_add_u32_e32 v130, v191, v102
	v_add_u32_e32 v132, v187, v102
	v_or_b32_e32 v185, 0x800, v191
	v_or_b32_e32 v184, 0xc00, v191
	v_or_b32_e32 v182, 0x2000, v191
	v_or_b32_e32 v180, 0x2400, v191
	v_or_b32_e32 v71, 0x2800, v191
	v_or_b32_e32 v181, 0x2c00, v191
	v_or_b32_e32 v183, 0x4000, v191
	v_add_u32_e32 v112, v186, v102
	v_or_b32_e32 v188, 0x4800, v191
	v_add_u32_e32 v116, v189, v102
	v_or_b32_e32 v190, 0x6000, v191
	v_or_b32_e32 v192, 0x6400, v191
	v_or_b32_e32 v193, 0x6800, v191
	v_add_u32_e32 v128, v194, v102
	s_addc_u32 s65, s69, 0
	global_load_dword v195, v[74:75], off
	v_lshl_add_u64 v[74:75], s[62:63], 0, v[72:73]
	v_ashrrev_i32_e32 v133, 31, v132
	v_add_u32_e32 v134, v185, v102
	v_add_u32_e32 v136, v184, v102
	v_add_u32_e32 v126, v182, v102
	v_add_u32_e32 v118, v180, v102
	v_add_u32_e32 v110, v71, v102
	v_add_u32_e32 v106, v181, v102
	v_add_u32_e32 v108, v183, v102
	v_ashrrev_i32_e32 v113, 31, v112
	v_add_u32_e32 v114, v188, v102
	v_ashrrev_i32_e32 v117, 31, v116
	v_add_u32_e32 v120, v190, v102
	v_add_u32_e32 v122, v192, v102
	v_add_u32_e32 v124, v193, v102
	v_ashrrev_i32_e32 v129, 31, v128
	v_ashrrev_i32_e32 v131, 31, v130
	v_lshl_add_u64 v[72:73], s[64:65], 0, v[72:73]
	global_load_dword v196, v[74:75], off
	global_load_dword v197, v[72:73], off
	v_lshl_add_u64 v[88:89], v[132:133], 2, s[12:13]
	v_ashrrev_i32_e32 v135, 31, v134
	v_ashrrev_i32_e32 v137, 31, v136
	v_ashrrev_i32_e32 v127, 31, v126
	v_ashrrev_i32_e32 v119, 31, v118
	v_ashrrev_i32_e32 v111, 31, v110
	v_ashrrev_i32_e32 v107, 31, v106
	v_ashrrev_i32_e32 v109, 31, v108
	v_lshl_add_u64 v[86:87], v[112:113], 2, s[12:13]
	v_ashrrev_i32_e32 v115, 31, v114
	v_lshl_add_u64 v[92:93], v[116:117], 2, s[12:13]
	v_ashrrev_i32_e32 v121, 31, v120
	v_ashrrev_i32_e32 v123, 31, v122
	v_ashrrev_i32_e32 v125, 31, v124
	v_lshl_add_u64 v[100:101], v[128:129], 2, s[12:13]
	v_lshl_add_u64 v[104:105], v[130:131], 2, s[12:13]
	v_lshl_add_u64 v[84:85], v[134:135], 2, s[12:13]
	v_lshl_add_u64 v[82:83], v[136:137], 2, s[12:13]
	v_lshl_add_u64 v[78:79], v[126:127], 2, s[12:13]
	v_lshl_add_u64 v[72:73], v[118:119], 2, s[12:13]
	v_lshl_add_u64 v[74:75], v[110:111], 2, s[12:13]
	v_lshl_add_u64 v[76:77], v[106:107], 2, s[12:13]
	v_lshl_add_u64 v[80:81], v[108:109], 2, s[12:13]
	global_load_dword v179, v[88:89], off
	global_load_dword v178, v[84:85], off
	global_load_dword v177, v[82:83], off
	global_load_dword v176, v[78:79], off
	global_load_dword v175, v[72:73], off
	global_load_dword v174, v[74:75], off
	global_load_dword v173, v[76:77], off
	global_load_dword v172, v[80:81], off
	v_lshl_add_u64 v[90:91], v[114:115], 2, s[12:13]
	global_load_dword v171, v[86:87], off
	global_load_dword v169, v[90:91], off
	v_lshl_add_u64 v[94:95], v[120:121], 2, s[12:13]
	v_lshl_add_u64 v[96:97], v[122:123], 2, s[12:13]
	v_lshl_add_u64 v[98:99], v[124:125], 2, s[12:13]
	global_load_dword v170, v[92:93], off
	global_load_dword v168, v[94:95], off
	global_load_dword v167, v[96:97], off
	global_load_dword v166, v[98:99], off
	global_load_dword v103, v[100:101], off
	global_load_dword v198, v[104:105], off
	v_lshl_add_u64 v[110:111], v[110:111], 1, s[8:9]
	v_lshl_add_u64 v[106:107], v[106:107], 1, s[8:9]
	s_waitcnt vmcnt(0)
	v_add_f32_e32 v197, 1.0, v197
	v_mul_f32_e32 v196, v196, v197
	v_fmac_f32_e32 v179, v49, v195
	v_fmac_f32_e32 v178, v50, v195
	v_fmac_f32_e32 v177, v51, v195
	v_fmac_f32_e32 v176, v52, v195
	v_fmac_f32_e32 v175, v53, v195
	v_fmac_f32_e32 v174, v54, v195
	v_fmac_f32_e32 v173, v55, v195
	v_fmac_f32_e32 v172, v56, v195
	v_fmac_f32_e32 v171, v57, v195
	v_fmac_f32_e32 v169, v58, v195
	v_fmac_f32_e32 v170, v59, v195
	v_fmac_f32_e32 v168, v60, v195
	v_fmac_f32_e32 v167, v61, v195
	v_fmac_f32_e32 v166, v62, v195
	v_fmac_f32_e32 v103, v63, v195
	v_fmac_f32_e32 v198, v48, v195
	v_mul_f32_e32 v48, v196, v198
	v_cvt_pk_bf16_f32 v58, v48, s0
	v_or_b32_e32 v48, 32, v102
	v_ashrrev_i32_e32 v49, 31, v48
	v_lshlrev_b64 v[52:53], 2, v[48:49]
	global_store_dword v[88:89], v179, off sc1
	global_store_dword v[84:85], v178, off sc1
	global_store_dword v[82:83], v177, off sc1
	global_store_dword v[78:79], v176, off sc1
	global_store_dword v[72:73], v175, off sc1
	global_store_dword v[74:75], v174, off sc1
	global_store_dword v[76:77], v173, off sc1
	global_store_dword v[80:81], v172, off sc1
	global_store_dword v[86:87], v171, off sc1
	global_store_dword v[90:91], v169, off sc1
	global_store_dword v[92:93], v170, off sc1
	global_store_dword v[94:95], v168, off sc1
	global_store_dword v[96:97], v167, off sc1
	global_store_dword v[98:99], v166, off sc1
	global_store_dword v[100:101], v103, off sc1
	global_store_dword v[104:105], v198, off sc1
	v_lshl_add_u64 v[50:51], v[130:131], 1, s[8:9]
	v_lshl_add_u64 v[56:57], s[64:65], 0, v[52:53]
	global_load_dword v197, v[104:105], off offset:128
	v_lshl_add_u64 v[54:55], s[62:63], 0, v[52:53]
	global_load_dword v130, v[56:57], off
	global_load_dword v131, v[54:55], off
	v_mul_f32_e32 v49, v196, v179
	global_store_short v[50:51], v58, off sc1
	v_lshl_add_u64 v[50:51], s[60:61], 0, v[52:53]
	global_load_dword v195, v[50:51], off
	v_lshl_add_u64 v[50:51], v[132:133], 1, s[8:9]
	v_cvt_pk_bf16_f32 v49, v49, s0
	global_store_short v[50:51], v49, off sc1
	v_mul_f32_e32 v49, v196, v178
	v_lshl_add_u64 v[50:51], v[134:135], 1, s[8:9]
	v_cvt_pk_bf16_f32 v49, v49, s0
	global_store_short v[50:51], v49, off sc1
	v_mul_f32_e32 v49, v196, v177
	v_lshl_add_u64 v[50:51], v[136:137], 1, s[8:9]
	v_cvt_pk_bf16_f32 v49, v49, s0
	global_store_short v[50:51], v49, off sc1
	v_mul_f32_e32 v49, v196, v176
	v_lshl_add_u64 v[50:51], v[126:127], 1, s[8:9]
	v_cvt_pk_bf16_f32 v49, v49, s0
	global_store_short v[50:51], v49, off sc1
	v_mul_f32_e32 v49, v196, v175
	v_lshl_add_u64 v[50:51], v[118:119], 1, s[8:9]
	v_cvt_pk_bf16_f32 v49, v49, s0
	global_load_dword v62, v[84:85], off offset:128
	global_load_dword v60, v[78:79], off offset:128
	global_load_dword v59, v[72:73], off offset:128
	global_load_dword v58, v[74:75], off offset:128
	global_load_dword v56, v[80:81], off offset:128
	global_load_dword v57, v[76:77], off offset:128
	global_load_dword v55, v[86:87], off offset:128
	global_load_dword v61, v[82:83], off offset:128
	global_load_dword v54, v[90:91], off offset:128
	global_load_dword v53, v[92:93], off offset:128
	global_load_dword v52, v[94:95], off offset:128
	v_mul_f32_e32 v63, v196, v174
	global_store_short v[50:51], v49, off sc1
	global_load_dword v51, v[96:97], off offset:128
	v_cvt_pk_bf16_f32 v63, v63, s0
	global_load_dword v50, v[98:99], off offset:128
	global_load_dword v49, v[100:101], off offset:128
	s_waitcnt vmcnt(19)
	v_fmac_f32_e32 v197, v32, v195
	global_store_short v[110:111], v63, off sc1
	global_load_dword v63, v[88:89], off offset:128
	v_mul_f32_e32 v110, v196, v173
	v_cvt_pk_bf16_f32 v110, v110, s0
	global_store_short v[106:107], v110, off sc1
	v_lshl_add_u64 v[106:107], v[108:109], 1, s[8:9]
	v_mul_f32_e32 v108, v196, v172
	v_cvt_pk_bf16_f32 v108, v108, s0
	global_store_short v[106:107], v108, off sc1
	v_mul_f32_e32 v108, v196, v171
	v_lshl_add_u64 v[106:107], v[112:113], 1, s[8:9]
	v_cvt_pk_bf16_f32 v108, v108, s0
	global_store_short v[106:107], v108, off sc1
	v_mul_f32_e32 v108, v196, v169
	v_lshl_add_u64 v[106:107], v[114:115], 1, s[8:9]
	v_cvt_pk_bf16_f32 v108, v108, s0
	global_store_short v[106:107], v108, off sc1
	v_mul_f32_e32 v108, v196, v170
	v_lshl_add_u64 v[106:107], v[116:117], 1, s[8:9]
	v_cvt_pk_bf16_f32 v108, v108, s0
	global_store_short v[106:107], v108, off sc1
	v_mul_f32_e32 v108, v196, v168
	v_lshl_add_u64 v[106:107], v[120:121], 1, s[8:9]
	v_cvt_pk_bf16_f32 v108, v108, s0
	global_store_short v[106:107], v108, off sc1
	v_mul_f32_e32 v108, v196, v167
	v_lshl_add_u64 v[106:107], v[122:123], 1, s[8:9]
	v_cvt_pk_bf16_f32 v108, v108, s0
	global_store_short v[106:107], v108, off sc1
	v_mul_f32_e32 v108, v196, v166
	v_lshl_add_u64 v[106:107], v[124:125], 1, s[8:9]
	v_cvt_pk_bf16_f32 v108, v108, s0
	global_store_short v[106:107], v108, off sc1
	v_mul_f32_e32 v108, v196, v103
	v_lshl_add_u64 v[106:107], v[128:129], 1, s[8:9]
	v_cvt_pk_bf16_f32 v108, v108, s0
	global_store_short v[106:107], v108, off sc1
	v_add_f32_e32 v106, 1.0, v130
	v_mul_f32_e32 v107, v131, v106
	v_add_u32_e32 v108, v191, v48
	v_ashrrev_i32_e32 v109, 31, v108
	v_mul_f32_e32 v32, v107, v197
	s_waitcnt vmcnt(25)
	v_fmac_f32_e32 v62, v34, v195
	s_waitcnt vmcnt(18)
	v_fmac_f32_e32 v61, v35, v195
	v_fmac_f32_e32 v60, v36, v195
	v_fmac_f32_e32 v59, v37, v195
	v_fmac_f32_e32 v58, v38, v195
	v_fmac_f32_e32 v57, v39, v195
	v_fmac_f32_e32 v56, v40, v195
	v_fmac_f32_e32 v55, v41, v195
	s_waitcnt vmcnt(17)
	v_fmac_f32_e32 v54, v42, v195
	s_waitcnt vmcnt(16)
	v_fmac_f32_e32 v53, v43, v195
	s_waitcnt vmcnt(15)
	v_fmac_f32_e32 v52, v44, v195
	s_waitcnt vmcnt(13)
	v_fmac_f32_e32 v51, v45, v195
	s_waitcnt vmcnt(12)
	v_fmac_f32_e32 v50, v46, v195
	s_waitcnt vmcnt(11)
	v_fmac_f32_e32 v49, v47, v195
	global_store_dword v[104:105], v197, off offset:128 sc1
	v_lshl_add_u64 v[108:109], v[108:109], 1, s[8:9]
	v_cvt_pk_bf16_f32 v32, v32, s0
	global_store_dword v[84:85], v62, off offset:128 sc1
	global_store_dword v[82:83], v61, off offset:128 sc1
	global_store_dword v[78:79], v60, off offset:128 sc1
	global_store_dword v[72:73], v59, off offset:128 sc1
	global_store_dword v[74:75], v58, off offset:128 sc1
	global_store_dword v[76:77], v57, off offset:128 sc1
	global_store_dword v[80:81], v56, off offset:128 sc1
	global_store_dword v[86:87], v55, off offset:128 sc1
	global_store_dword v[90:91], v54, off offset:128 sc1
	global_store_dword v[92:93], v53, off offset:128 sc1
	global_store_dword v[94:95], v52, off offset:128 sc1
	global_store_dword v[96:97], v51, off offset:128 sc1
	global_store_dword v[98:99], v50, off offset:128 sc1
	global_store_dword v[100:101], v49, off offset:128 sc1
	global_store_short v[108:109], v32, off sc1
	v_add_u32_e32 v108, v187, v48
	global_load_dword v45, v[88:89], off offset:256
	v_ashrrev_i32_e32 v109, 31, v108
	v_mul_f32_e32 v113, v107, v56
	v_cvt_pk_bf16_f32 v113, v113, s0
	v_mul_f32_e32 v106, v197, v197
	v_fmac_f32_e32 v106, v198, v198
	s_waitcnt vmcnt(26)
	v_fmac_f32_e32 v63, v33, v195
	v_mul_f32_e32 v34, v107, v63
	v_lshl_add_u64 v[32:33], v[108:109], 1, s[8:9]
	v_cvt_pk_bf16_f32 v34, v34, s0
	global_store_short v[32:33], v34, off sc1
	v_add_u32_e32 v32, v185, v48
	v_ashrrev_i32_e32 v33, 31, v32
	v_mul_f32_e32 v34, v107, v62
	v_lshl_add_u64 v[32:33], v[32:33], 1, s[8:9]
	v_cvt_pk_bf16_f32 v34, v34, s0
	global_store_short v[32:33], v34, off sc1
	v_add_u32_e32 v32, v184, v48
	v_ashrrev_i32_e32 v33, 31, v32
	v_mul_f32_e32 v34, v107, v61
	v_lshl_add_u64 v[32:33], v[32:33], 1, s[8:9]
	v_cvt_pk_bf16_f32 v34, v34, s0
	global_store_short v[32:33], v34, off sc1
	v_add_u32_e32 v32, v182, v48
	v_ashrrev_i32_e32 v33, 31, v32
	v_mul_f32_e32 v34, v107, v60
	v_lshl_add_u64 v[32:33], v[32:33], 1, s[8:9]
	v_cvt_pk_bf16_f32 v34, v34, s0
	global_store_short v[32:33], v34, off sc1
	v_add_u32_e32 v32, v180, v48
	v_ashrrev_i32_e32 v33, 31, v32
	v_lshl_add_u64 v[34:35], v[32:33], 1, s[8:9]
	v_mul_f32_e32 v32, v107, v59
	v_cvt_pk_bf16_f32 v42, v32, s0
	v_or_b32_e32 v32, 64, v102
	v_ashrrev_i32_e32 v33, 31, v32
	v_lshlrev_b64 v[36:37], 2, v[32:33]
	global_store_dword v[88:89], v63, off offset:128 sc1
	v_lshl_add_u64 v[40:41], s[64:65], 0, v[36:37]
	v_lshl_add_u64 v[38:39], s[62:63], 0, v[36:37]
	global_load_dword v110, v[40:41], off
	global_load_dword v111, v[38:39], off
	v_mul_f32_e32 v33, v107, v58
	global_store_short v[34:35], v42, off sc1
	v_lshl_add_u64 v[34:35], s[60:61], 0, v[36:37]
	global_load_dword v112, v[34:35], off
	v_add_u32_e32 v34, v71, v48
	v_ashrrev_i32_e32 v35, 31, v34
	v_lshl_add_u64 v[34:35], v[34:35], 1, s[8:9]
	v_cvt_pk_bf16_f32 v33, v33, s0
	global_store_short v[34:35], v33, off sc1
	v_add_u32_e32 v34, v181, v48
	v_ashrrev_i32_e32 v35, 31, v34
	v_mul_f32_e32 v33, v107, v57
	v_lshl_add_u64 v[34:35], v[34:35], 1, s[8:9]
	v_cvt_pk_bf16_f32 v33, v33, s0
	global_load_dword v38, v[90:91], off offset:256
	global_load_dword v37, v[92:93], off offset:256
	global_load_dword v36, v[94:95], off offset:256
	global_load_dword v114, v[104:105], off offset:256
	global_load_dword v47, v[84:85], off offset:256
	global_load_dword v39, v[86:87], off offset:256
	global_load_dword v46, v[82:83], off offset:256
	global_load_dword v44, v[78:79], off offset:256
	global_load_dword v43, v[72:73], off offset:256
	global_load_dword v42, v[74:75], off offset:256
	global_load_dword v40, v[80:81], off offset:256
	global_load_dword v41, v[76:77], off offset:256
	v_add_u32_e32 v108, v183, v48
	global_store_short v[34:35], v33, off sc1
	global_load_dword v35, v[96:97], off offset:256
	v_ashrrev_i32_e32 v109, 31, v108
	global_load_dword v34, v[98:99], off offset:256
	global_load_dword v33, v[100:101], off offset:256
	v_lshl_add_u64 v[108:109], v[108:109], 1, s[8:9]
	global_store_short v[108:109], v113, off sc1
	v_add_u32_e32 v108, v186, v48
	v_ashrrev_i32_e32 v109, 31, v108
	v_mul_f32_e32 v113, v107, v55
	v_lshl_add_u64 v[108:109], v[108:109], 1, s[8:9]
	v_cvt_pk_bf16_f32 v113, v113, s0
	global_store_short v[108:109], v113, off sc1
	v_add_u32_e32 v108, v188, v48
	v_ashrrev_i32_e32 v109, 31, v108
	v_mul_f32_e32 v113, v107, v54
	v_lshl_add_u64 v[108:109], v[108:109], 1, s[8:9]
	v_cvt_pk_bf16_f32 v113, v113, s0
	global_store_short v[108:109], v113, off sc1
	v_add_u32_e32 v108, v189, v48
	v_ashrrev_i32_e32 v109, 31, v108
	v_mul_f32_e32 v113, v107, v53
	v_lshl_add_u64 v[108:109], v[108:109], 1, s[8:9]
	v_cvt_pk_bf16_f32 v113, v113, s0
	global_store_short v[108:109], v113, off sc1
	v_add_u32_e32 v108, v190, v48
	v_ashrrev_i32_e32 v109, 31, v108
	v_mul_f32_e32 v113, v107, v52
	v_lshl_add_u64 v[108:109], v[108:109], 1, s[8:9]
	v_cvt_pk_bf16_f32 v113, v113, s0
	global_store_short v[108:109], v113, off sc1
	v_add_u32_e32 v108, v192, v48
	v_ashrrev_i32_e32 v109, 31, v108
	v_mul_f32_e32 v113, v107, v51
	v_lshl_add_u64 v[108:109], v[108:109], 1, s[8:9]
	v_cvt_pk_bf16_f32 v113, v113, s0
	global_store_short v[108:109], v113, off sc1
	v_add_u32_e32 v108, v193, v48
	v_ashrrev_i32_e32 v109, 31, v108
	v_mul_f32_e32 v113, v107, v50
	v_lshl_add_u64 v[108:109], v[108:109], 1, s[8:9]
	v_cvt_pk_bf16_f32 v113, v113, s0
	global_store_short v[108:109], v113, off sc1
	v_add_u32_e32 v108, v194, v48
	v_ashrrev_i32_e32 v109, 31, v108
	v_mul_f32_e32 v48, v107, v49
	v_lshl_add_u64 v[108:109], v[108:109], 1, s[8:9]
	v_cvt_pk_bf16_f32 v48, v48, s0
	global_store_short v[108:109], v48, off sc1
	v_add_u32_e32 v108, v191, v32
	v_ashrrev_i32_e32 v109, 31, v108
	s_waitcnt vmcnt(28)
	v_add_f32_e32 v48, 1.0, v110
	s_waitcnt vmcnt(27)
	v_mul_f32_e32 v48, v111, v48
	s_waitcnt vmcnt(25)
	v_fmac_f32_e32 v45, v17, v112
	global_store_dword v[88:89], v45, off offset:256 sc1
	s_waitcnt vmcnt(24)
	v_fmac_f32_e32 v38, v26, v112
	s_waitcnt vmcnt(23)
	v_fmac_f32_e32 v37, v27, v112
	s_waitcnt vmcnt(22)
	v_fmac_f32_e32 v36, v28, v112
	s_waitcnt vmcnt(21)
	v_fmac_f32_e32 v114, v16, v112
	s_waitcnt vmcnt(20)
	v_fmac_f32_e32 v47, v18, v112
	v_mul_f32_e32 v18, v48, v114
	v_lshl_add_u64 v[16:17], v[108:109], 1, s[8:9]
	v_cvt_pk_bf16_f32 v18, v18, s0
	global_store_short v[16:17], v18, off sc1
	v_add_u32_e32 v16, v187, v32
	v_ashrrev_i32_e32 v17, 31, v16
	v_mul_f32_e32 v18, v48, v45
	v_lshl_add_u64 v[16:17], v[16:17], 1, s[8:9]
	v_cvt_pk_bf16_f32 v18, v18, s0
	global_store_short v[16:17], v18, off sc1
	v_add_u32_e32 v16, v185, v32
	v_ashrrev_i32_e32 v17, 31, v16
	v_mul_f32_e32 v18, v48, v47
	v_lshl_add_u64 v[16:17], v[16:17], 1, s[8:9]
	v_cvt_pk_bf16_f32 v18, v18, s0
	s_waitcnt vmcnt(20)
	v_fmac_f32_e32 v46, v19, v112
	global_store_short v[16:17], v18, off sc1
	v_add_u32_e32 v16, v184, v32
	v_ashrrev_i32_e32 v17, 31, v16
	v_mul_f32_e32 v18, v48, v46
	v_lshl_add_u64 v[16:17], v[16:17], 1, s[8:9]
	v_cvt_pk_bf16_f32 v18, v18, s0
	global_store_short v[16:17], v18, off sc1
	v_add_u32_e32 v16, v182, v32
	v_ashrrev_i32_e32 v17, 31, v16
	v_lshl_add_u64 v[18:19], v[16:17], 1, s[8:9]
	v_or_b32_e32 v16, 0x60, v102
	v_ashrrev_i32_e32 v17, 31, v16
	s_waitcnt vmcnt(21)
	v_fmac_f32_e32 v44, v20, v112
	s_waitcnt vmcnt(20)
	v_fmac_f32_e32 v43, v21, v112
	s_waitcnt vmcnt(19)
	v_fmac_f32_e32 v42, v22, v112
	s_waitcnt vmcnt(17)
	v_fmac_f32_e32 v41, v23, v112
	v_fmac_f32_e32 v40, v24, v112
	v_fmac_f32_e32 v39, v25, v112
	s_waitcnt vmcnt(15)
	v_fmac_f32_e32 v35, v29, v112
	s_waitcnt vmcnt(14)
	v_fmac_f32_e32 v34, v30, v112
	s_waitcnt vmcnt(13)
	v_fmac_f32_e32 v33, v31, v112
	v_lshlrev_b64 v[20:21], 2, v[16:17]
	global_store_dword v[84:85], v47, off offset:256 sc1
	global_store_dword v[82:83], v46, off offset:256 sc1
	global_store_dword v[78:79], v44, off offset:256 sc1
	global_store_dword v[72:73], v43, off offset:256 sc1
	global_store_dword v[74:75], v42, off offset:256 sc1
	global_store_dword v[76:77], v41, off offset:256 sc1
	global_store_dword v[80:81], v40, off offset:256 sc1
	global_store_dword v[86:87], v39, off offset:256 sc1
	global_store_dword v[90:91], v38, off offset:256 sc1
	global_store_dword v[92:93], v37, off offset:256 sc1
	global_store_dword v[94:95], v36, off offset:256 sc1
	global_store_dword v[96:97], v35, off offset:256 sc1
	global_store_dword v[98:99], v34, off offset:256 sc1
	global_store_dword v[100:101], v33, off offset:256 sc1
	global_store_dword v[104:105], v114, off offset:256 sc1
	v_mul_f32_e32 v26, v48, v44
	v_lshl_add_u64 v[22:23], s[62:63], 0, v[20:21]
	v_lshl_add_u64 v[24:25], s[64:65], 0, v[20:21]
	global_load_dword v29, v[104:105], off offset:384
	global_load_dword v17, v[24:25], off
	global_load_dword v30, v[22:23], off
	v_cvt_pk_bf16_f32 v22, v26, s0
	global_store_short v[18:19], v22, off sc1
	v_lshl_add_u64 v[18:19], s[60:61], 0, v[20:21]
	global_load_dword v102, v[18:19], off
	v_add_u32_e32 v18, v180, v32
	v_ashrrev_i32_e32 v19, 31, v18
	v_mul_f32_e32 v20, v48, v43
	v_lshl_add_u64 v[18:19], v[18:19], 1, s[8:9]
	v_cvt_pk_bf16_f32 v20, v20, s0
	global_store_short v[18:19], v20, off sc1
	v_add_u32_e32 v18, v71, v32
	v_ashrrev_i32_e32 v19, 31, v18
	v_mul_f32_e32 v20, v48, v42
	v_lshl_add_u64 v[18:19], v[18:19], 1, s[8:9]
	v_cvt_pk_bf16_f32 v20, v20, s0
	global_store_short v[18:19], v20, off sc1
	v_add_u32_e32 v18, v181, v32
	v_ashrrev_i32_e32 v19, 31, v18
	v_mul_f32_e32 v20, v48, v41
	v_lshl_add_u64 v[18:19], v[18:19], 1, s[8:9]
	v_cvt_pk_bf16_f32 v20, v20, s0
	global_store_short v[18:19], v20, off sc1
	v_add_u32_e32 v18, v183, v32
	v_ashrrev_i32_e32 v19, 31, v18
	v_mul_f32_e32 v20, v48, v40
	v_lshl_add_u64 v[18:19], v[18:19], 1, s[8:9]
	v_cvt_pk_bf16_f32 v20, v20, s0
	global_store_short v[18:19], v20, off sc1
	v_add_u32_e32 v18, v186, v32
	v_ashrrev_i32_e32 v19, 31, v18
	v_mul_f32_e32 v20, v48, v39
	v_lshl_add_u64 v[18:19], v[18:19], 1, s[8:9]
	v_cvt_pk_bf16_f32 v20, v20, s0
	global_store_short v[18:19], v20, off sc1
	v_add_u32_e32 v18, v188, v32
	v_ashrrev_i32_e32 v19, 31, v18
	v_mul_f32_e32 v20, v48, v38
	v_lshl_add_u64 v[18:19], v[18:19], 1, s[8:9]
	v_cvt_pk_bf16_f32 v20, v20, s0
	global_store_short v[18:19], v20, off sc1
	v_add_u32_e32 v18, v189, v32
	v_ashrrev_i32_e32 v19, 31, v18
	v_mul_f32_e32 v20, v48, v37
	v_lshl_add_u64 v[18:19], v[18:19], 1, s[8:9]
	v_cvt_pk_bf16_f32 v20, v20, s0
	global_store_short v[18:19], v20, off sc1
	v_add_u32_e32 v18, v190, v32
	v_ashrrev_i32_e32 v19, 31, v18
	v_mul_f32_e32 v20, v48, v36
	v_lshl_add_u64 v[18:19], v[18:19], 1, s[8:9]
	v_cvt_pk_bf16_f32 v20, v20, s0
	global_store_short v[18:19], v20, off sc1
	v_add_u32_e32 v18, v192, v32
	v_ashrrev_i32_e32 v19, 31, v18
	v_mul_f32_e32 v20, v48, v35
	v_lshl_add_u64 v[18:19], v[18:19], 1, s[8:9]
	v_cvt_pk_bf16_f32 v20, v20, s0
	global_load_dword v28, v[88:89], off offset:384
	global_load_dword v27, v[84:85], off offset:384
	global_load_dword v25, v[78:79], off offset:384
	global_load_dword v24, v[72:73], off offset:384
	global_load_dword v23, v[74:75], off offset:384
	global_load_dword v21, v[80:81], off offset:384
	global_load_dword v22, v[76:77], off offset:384
	v_fmac_f32_e32 v106, v114, v114
	global_store_short v[18:19], v20, off sc1
	v_add_u32_e32 v18, v193, v32
	v_ashrrev_i32_e32 v19, 31, v18
	v_mul_f32_e32 v20, v48, v34
	v_lshl_add_u64 v[18:19], v[18:19], 1, s[8:9]
	v_cvt_pk_bf16_f32 v20, v20, s0
	global_store_short v[18:19], v20, off sc1
	v_add_u32_e32 v18, v194, v32
	v_ashrrev_i32_e32 v19, 31, v18
	v_mul_f32_e32 v20, v48, v33
	v_lshl_add_u64 v[18:19], v[18:19], 1, s[8:9]
	v_cvt_pk_bf16_f32 v20, v20, s0
	global_store_short v[18:19], v20, off sc1
	global_load_dword v20, v[86:87], off offset:384
	s_waitcnt vmcnt(22)
	v_add_f32_e32 v17, 1.0, v17
	global_load_dword v26, v[82:83], off offset:384
	s_waitcnt vmcnt(22)
	v_mul_f32_e32 v32, v30, v17
	v_add_u32_e32 v18, v191, v16
	s_waitcnt vmcnt(20)
	v_fmac_f32_e32 v29, v0, v102
	v_ashrrev_i32_e32 v19, 31, v18
	v_mul_f32_e32 v0, v32, v29
	v_lshl_add_u64 v[18:19], v[18:19], 1, s[8:9]
	v_cvt_pk_bf16_f32 v0, v0, s0
	global_store_short v[18:19], v0, off sc1
	global_load_dword v19, v[90:91], off offset:384
	v_add_u32_e32 v30, v187, v16
	global_load_dword v18, v[92:93], off offset:384
	v_ashrrev_i32_e32 v31, 31, v30
	v_fmac_f32_e32 v106, v29, v29
	global_store_dword v[104:105], v29, off offset:384 sc1
	s_waitcnt vmcnt(15)
	v_fmac_f32_e32 v28, v1, v102
	v_mul_f32_e32 v17, v32, v28
	v_lshl_add_u64 v[0:1], v[30:31], 1, s[8:9]
	v_cvt_pk_bf16_f32 v17, v17, s0
	global_store_short v[0:1], v17, off sc1
	v_add_u32_e32 v0, v185, v16
	s_waitcnt vmcnt(15)
	v_fmac_f32_e32 v27, v2, v102
	global_load_dword v17, v[94:95], off offset:384
	v_ashrrev_i32_e32 v1, 31, v0
	v_mul_f32_e32 v2, v32, v27
	v_lshl_add_u64 v[0:1], v[0:1], 1, s[8:9]
	v_cvt_pk_bf16_f32 v2, v2, s0
	global_store_short v[0:1], v2, off sc1
	v_add_u32_e32 v0, v184, v16
	global_load_dword v2, v[96:97], off offset:384
	v_ashrrev_i32_e32 v1, 31, v0
	v_lshl_add_u64 v[0:1], v[0:1], 1, s[8:9]
	v_add_u32_e32 v30, v182, v16
	s_waitcnt vmcnt(17)
	v_fmac_f32_e32 v25, v4, v102
	v_ashrrev_i32_e32 v31, 31, v30
	v_lshl_add_u64 v[30:31], v[30:31], 1, s[8:9]
	s_waitcnt vmcnt(16)
	v_fmac_f32_e32 v24, v5, v102
	s_waitcnt vmcnt(15)
	v_fmac_f32_e32 v23, v6, v102
	s_waitcnt vmcnt(8)
	v_fmac_f32_e32 v26, v3, v102
	v_mul_f32_e32 v3, v32, v26
	v_cvt_pk_bf16_f32 v3, v3, s0
	global_store_short v[0:1], v3, off sc1
	global_load_dword v1, v[98:99], off offset:384
	v_mul_f32_e32 v0, v32, v25
	v_cvt_pk_bf16_f32 v0, v0, s0
	global_store_short v[30:31], v0, off sc1
	global_load_dword v0, v[100:101], off offset:384
	v_add_u32_e32 v30, v180, v16
	v_ashrrev_i32_e32 v31, 31, v30
	v_mul_f32_e32 v3, v32, v24
	v_lshl_add_u64 v[4:5], v[30:31], 1, s[8:9]
	v_cvt_pk_bf16_f32 v3, v3, s0
	global_store_short v[4:5], v3, off sc1
	v_add_u32_e32 v4, v71, v16
	v_ashrrev_i32_e32 v5, 31, v4
	v_mul_f32_e32 v3, v32, v23
	v_lshl_add_u64 v[4:5], v[4:5], 1, s[8:9]
	v_cvt_pk_bf16_f32 v3, v3, s0
	global_store_short v[4:5], v3, off sc1
	v_add_u32_e32 v4, v181, v16
	v_fmac_f32_e32 v22, v7, v102
	v_ashrrev_i32_e32 v5, 31, v4
	v_mul_f32_e32 v3, v32, v22
	v_lshl_add_u64 v[4:5], v[4:5], 1, s[8:9]
	v_cvt_pk_bf16_f32 v3, v3, s0
	global_store_short v[4:5], v3, off sc1
	v_add_u32_e32 v4, v183, v16
	v_fmac_f32_e32 v21, v8, v102
	v_ashrrev_i32_e32 v5, 31, v4
	v_mul_f32_e32 v3, v32, v21
	v_lshl_add_u64 v[4:5], v[4:5], 1, s[8:9]
	v_cvt_pk_bf16_f32 v3, v3, s0
	global_store_short v[4:5], v3, off sc1
	v_add_u32_e32 v4, v186, v16
	v_fmac_f32_e32 v20, v9, v102
	v_ashrrev_i32_e32 v5, 31, v4
	v_mul_f32_e32 v3, v32, v20
	v_lshl_add_u64 v[4:5], v[4:5], 1, s[8:9]
	v_cvt_pk_bf16_f32 v3, v3, s0
	global_store_short v[4:5], v3, off sc1
	v_add_u32_e32 v4, v188, v16
	s_waitcnt vmcnt(15)
	v_fmac_f32_e32 v19, v10, v102
	v_ashrrev_i32_e32 v5, 31, v4
	v_mul_f32_e32 v3, v32, v19
	v_lshl_add_u64 v[4:5], v[4:5], 1, s[8:9]
	v_cvt_pk_bf16_f32 v3, v3, s0
	global_store_short v[4:5], v3, off sc1
	v_add_u32_e32 v4, v189, v16
	s_waitcnt vmcnt(15)
	v_fmac_f32_e32 v18, v11, v102
	v_ashrrev_i32_e32 v5, 31, v4
	v_mul_f32_e32 v3, v32, v18
	v_lshl_add_u64 v[4:5], v[4:5], 1, s[8:9]
	v_cvt_pk_bf16_f32 v3, v3, s0
	global_store_short v[4:5], v3, off sc1
	v_add_u32_e32 v4, v190, v16
	v_ashrrev_i32_e32 v5, 31, v4
	v_lshl_add_u64 v[4:5], v[4:5], 1, s[8:9]
	v_ashrrev_i32_e32 v71, 31, v70
	global_store_dword v[88:89], v28, off offset:384 sc1
	global_store_dword v[84:85], v27, off offset:384 sc1
	global_store_dword v[82:83], v26, off offset:384 sc1
	global_store_dword v[78:79], v25, off offset:384 sc1
	s_waitcnt vmcnt(17)
	v_fmac_f32_e32 v17, v12, v102
	v_mul_f32_e32 v3, v32, v17
	v_cvt_pk_bf16_f32 v3, v3, s0
	global_store_short v[4:5], v3, off sc1
	v_add_u32_e32 v4, v192, v16
	v_ashrrev_i32_e32 v5, 31, v4
	v_lshl_add_u64 v[4:5], v[4:5], 1, s[8:9]
	s_waitcnt vmcnt(16)
	v_fmac_f32_e32 v2, v13, v102
	v_mul_f32_e32 v3, v32, v2
	v_cvt_pk_bf16_f32 v3, v3, s0
	global_store_short v[4:5], v3, off sc1
	v_add_u32_e32 v4, v193, v16
	v_ashrrev_i32_e32 v5, 31, v4
	v_lshl_add_u64 v[4:5], v[4:5], 1, s[8:9]
	v_xor_b32_e32 v12, 16, v165
	global_store_dword v[72:73], v24, off offset:384 sc1
	global_store_dword v[74:75], v23, off offset:384 sc1
	global_store_dword v[76:77], v22, off offset:384 sc1
	global_store_dword v[80:81], v21, off offset:384 sc1
	global_store_dword v[86:87], v20, off offset:384 sc1
	s_waitcnt vmcnt(20)
	v_fmac_f32_e32 v1, v14, v102
	v_mul_f32_e32 v3, v32, v1
	v_cvt_pk_bf16_f32 v3, v3, s0
	global_store_short v[4:5], v3, off sc1
	v_add_u32_e32 v4, v194, v16
	v_ashrrev_i32_e32 v5, 31, v4
	v_lshl_add_u64 v[10:11], v[4:5], 1, s[8:9]
	v_and_b32_e32 v4, 64, v165
	v_xor_b32_e32 v3, 1, v165
	v_add_u32_e32 v7, 64, v4
	v_cmp_lt_i32_e32 vcc, v3, v7
	v_xor_b32_e32 v4, 2, v165
	s_waitcnt vmcnt(19)
	v_fmac_f32_e32 v0, v15, v102
	v_cndmask_b32_e32 v3, v165, v3, vcc
	v_lshlrev_b32_e32 v3, 2, v3
	ds_bpermute_b32 v5, v3, v106
	v_cmp_lt_i32_e32 vcc, v4, v7
	global_store_dword v[90:91], v19, off offset:384 sc1
	global_store_dword v[92:93], v18, off offset:384 sc1
	v_cndmask_b32_e32 v4, v165, v4, vcc
	v_lshlrev_b32_e32 v4, 2, v4
	s_waitcnt lgkmcnt(0)
	v_add_f32_e32 v6, v106, v5
	ds_bpermute_b32 v8, v4, v6
	v_xor_b32_e32 v5, 4, v165
	v_cmp_lt_i32_e32 vcc, v5, v7
	global_store_dword v[94:95], v17, off offset:384 sc1
	global_store_dword v[96:97], v2, off offset:384 sc1
	v_cndmask_b32_e32 v5, v165, v5, vcc
	v_lshlrev_b32_e32 v5, 2, v5
	s_waitcnt lgkmcnt(0)
	v_add_f32_e32 v8, v6, v8
	ds_bpermute_b32 v9, v5, v8
	v_xor_b32_e32 v6, 8, v165
	v_cmp_lt_i32_e32 vcc, v6, v7
	global_store_dword v[98:99], v1, off offset:384 sc1
	global_store_dword v[100:101], v0, off offset:384 sc1
	v_cndmask_b32_e32 v6, v165, v6, vcc
	v_lshlrev_b32_e32 v6, 2, v6
	s_waitcnt lgkmcnt(0)
	v_add_f32_e32 v8, v8, v9
	ds_bpermute_b32 v9, v6, v8
	v_cmp_lt_i32_e32 vcc, v12, v7
	s_waitcnt lgkmcnt(0)
	v_add_f32_e32 v8, v8, v9
	v_cndmask_b32_e32 v7, v165, v12, vcc
	v_lshlrev_b32_e32 v7, 2, v7
	ds_bpermute_b32 v9, v7, v8
	v_mul_f32_e32 v12, v32, v0
	v_cvt_pk_bf16_f32 v12, v12, s0
	global_store_short v[10:11], v12, off sc1
	s_and_saveexec_b64 s[60:61], s[0:1]
	s_cbranch_execz .LBB0_1400
	s_waitcnt lgkmcnt(0)
	v_add_f32_e32 v10, v8, v9
	v_lshl_add_u64 v[8:9], v[70:71], 2, s[58:59]
	global_store_dword v[8:9], v10, off sc1

.LBB0_1430:
	s_cmp_gt_i32 s17, 19
	s_cselect_b64 s[6:7], -1, 0
	s_and_b64 s[0:1], s[4:5], s[6:7]
	s_andn2_b64 vcc, exec, s[0:1]
	s_cbranch_vccnz .LBB0_1442
	s_waitcnt vmcnt(0)
	v_or_b32_e32 v0, v201, v200
	s_movk_i32 s0, 0x3ff
	v_and_or_b32 v0, v0, s0, v199
	v_cmp_eq_u32_e32 vcc, 0, v0
	s_waitcnt lgkmcnt(0)
	s_barrier
	s_and_saveexec_b64 s[0:1], vcc
	s_cbranch_execz .LBB0_1441
	s_add_u32 s4, s14, 0x5be8c00
	s_addc_u32 s5, s15, 0
	s_lshl_b32 s3, s2, 1
	v_mov_b32_e32 v0, s3
	v_mov_b32_e32 v1, 0x9313
	global_store_short v0, v1, s[4:5] sc1
	s_cmp_lg_u32 s2, 0
	s_cbranch_scc1 .Lgbar_wait_18
	s_lshr_b32 s3, s33, 3
	s_bfm_b64 s[8:9], s3, 0
	s_cmpk_gt_u32 s33, 0x1ff
	s_cselect_b64 s[8:9], -1, s[8:9]
	s_mov_b64 exec, -1
	v_mbcnt_lo_u32_b32 v229, -1, 0
	v_mbcnt_hi_u32_b32 v229, -1, v229
	v_lshlrev_b32_e32 v229, 4, v229
	s_mov_b32 s10, 0x93139313
	s_mov_b64 exec, s[8:9]

.LBB0_1442:
	s_cmp_lt_i32 s16, 20
	s_cselect_b64 s[0:1], -1, 0
	s_and_b64 s[4:5], s[0:1], s[6:7]
	s_andn2_b64 vcc, exec, s[4:5]
	s_cbranch_vccnz .LBB0_1454
	s_ashr_i32 s3, s2, 31
	s_and_b32 s3, s3, s33
	s_add_i32 s3, s3, s2
	s_cmpk_gt_i32 s3, 0x7ff
	s_cbranch_scc1 .LBB0_1454
	v_lshrrev_b32_e32 v0, 3, v199
	s_waitcnt lgkmcnt(0)
	v_lshrrev_b32_e32 v1, 5, v199
	v_bfe_u32 v4, v199, 1, 3
	v_lshlrev_b32_e32 v5, 4, v199
	v_bfe_u32 v2, v199, 5, 1
	v_xor_b32_e32 v6, v5, v199
	v_lshlrev_b32_e32 v7, 11, v0
	s_movk_i32 s4, 0x70
	v_bitop3_b32 v1, v1, v4, 1 bitop3:0x6c
	v_and_or_b32 v76, v6, s4, v7
	v_lshlrev_b32_e32 v7, 4, v1
	v_bitop3_b32 v1, v2, v4, 2 bitop3:0x36
	v_lshrrev_b32_e32 v3, 1, v199
	v_lshlrev_b32_e32 v9, 4, v1
	v_bitop3_b32 v1, v2, v4, 4 bitop3:0x36
	v_mov_b32_e32 v77, 0
	v_and_b32_e32 v3, 0x1e0, v3
	v_lshlrev_b32_e32 v10, 4, v1
	v_bitop3_b32 v1, v2, v4, 6 bitop3:0x36
	v_lshlrev_b32_e32 v2, 4, v1
	v_and_or_b32 v95, v0, 4, v3
	v_lshl_add_u64 v[0:1], s[14:15], 0, v[76:77]
	s_mov_b64 s[6:7], 0x679f000
	v_lshl_add_u64 v[78:79], v[0:1], 0, s[6:7]
	s_mov_b64 s[6:7], 0x12a0000
	v_lshl_add_u64 v[80:81], v[0:1], 0, s[6:7]
	s_add_u32 s6, s14, 0x5f4e000
	s_addc_u32 s7, s15, 0
	s_add_u32 s10, s14, 0x5c03000
	s_addc_u32 s11, s15, 0
	v_and_b32_e32 v94, 31, v199
	s_add_u32 s8, s14, 0x13f9f000
	v_or_b32_e32 v6, v3, v94
	s_addc_u32 s9, s15, 0
	v_lshl_add_u32 v6, v6, 7, 0
	v_lshl_add_u32 v8, v94, 7, 0
	s_add_u32 s18, s14, 0xdf9f000
	v_add_u32_e32 v97, 0, v5
	s_mov_b32 s5, 0
	v_or_b32_e32 v96, 0xfffffc00, v94
	s_addc_u32 s19, s15, 0
	v_add_u32_e32 v98, 0x4000, v97
	s_mov_b64 s[20:21], 0x10000
	v_add_u32_e32 v99, 0x1000, v97
	v_add_u32_e32 v100, 0x5000, v97
	s_mov_b64 s[22:23], 0x20000
	v_add_u32_e32 v101, 0x2000, v97
	v_add_u32_e32 v102, 0x6000, v97
	s_mov_b64 s[24:25], 0x30000
	v_add_u32_e32 v103, 0x3000, v97
	v_add_u32_e32 v104, 0x7000, v97
	s_mov_b64 s[26:27], 0x679f080
	s_mov_b64 s[28:29], 0x12a0080
	v_add_u32_e32 v105, 0x8000, v97
	v_add_u32_e32 v106, 0xc000, v97
	s_mov_b64 s[30:31], 0x67af080
	v_add_u32_e32 v107, 0x9000, v97
	s_mov_b64 s[34:35], 0x12b0080
	v_add_u32_e32 v108, 0xd000, v97
	s_mov_b64 s[36:37], 0x67bf080
	v_add_u32_e32 v109, 0xa000, v97
	s_mov_b64 s[38:39], 0x12c0080
	v_add_u32_e32 v110, 0xe000, v97
	s_mov_b64 s[40:41], 0x67cf080
	v_add_u32_e32 v111, 0xb000, v97
	s_mov_b64 s[42:43], 0x12d0080
	s_waitcnt vmcnt(5)
	v_add_u32_e32 v112, 0xf000, v97
	v_add_u32_e32 v113, v6, v7
	v_add_u32_e32 v114, v8, v7
	v_add_u32_e32 v115, v6, v9
	s_waitcnt vmcnt(4)
	v_add_u32_e32 v116, v8, v9
	v_add_u32_e32 v117, v6, v10
	v_add_u32_e32 v118, v8, v10
	v_add_u32_e32 v119, v6, v2
	s_waitcnt vmcnt(3)
	v_add_u32_e32 v120, v8, v2
	s_mov_b64 s[44:45], 0x679f100
	s_mov_b64 s[46:47], 0x12a0100
	s_mov_b64 s[48:49], 0x67af100
	s_mov_b64 s[50:51], 0x12b0100
	s_mov_b64 s[52:53], 0x67bf100
	s_mov_b64 s[54:55], 0x12c0100
	s_mov_b64 s[56:57], 0x67cf100
	s_mov_b64 s[58:59], 0x12d0100
	s_mov_b32 s70, 0x10000
	s_mov_b32 s71, 0x20000
	s_mov_b32 s72, 0x30000
	s_mov_b32 s73, 0x40000
	s_mov_b32 s74, 0x50000
	s_mov_b32 s75, 0x60000
	s_mov_b32 s76, 0x70000
	v_mov_b32_e32 v121, 0x358637bd
	s_mov_b32 s41, 0
	s_branch .LBB0_1446
.LBB0_1445:
	s_add_u32 s60, s14, s60
	s_addc_u32 s61, s15, s61
	v_ashrrev_i32_e32 v1, 31, v0
	s_add_i32 s3, s3, s33
	v_cvt_pk_bf16_f32 v2, v65, s0
	v_lshl_add_u64 v[0:1], v[0:1], 1, s[60:61]
	s_cmpk_gt_i32 s3, 0x7ff
	global_store_short v[0:1], v2, off sc1
	s_cbranch_scc1 .LBB0_1454
.LBB0_1446:
	s_ashr_i32 s4, s3, 31
	s_lshr_b32 s4, s4, 25
	s_add_i32 s4, s3, s4
	s_ashr_i32 s60, s4, 7
	s_and_b32 s4, s4, 0xffffff80
	s_sub_i32 s77, s3, s4
	s_ashr_i32 s4, s77, 31
	s_lshr_b32 s4, s4, 29
	s_add_i32 s61, s77, s4
	s_and_b32 s4, s61, -8
	s_lshl_b32 s60, s60, 3
	s_sub_i32 s4, s77, s4
	s_add_i32 s4, s4, s60
	s_lshl_b32 s60, s61, 4
	s_lshl_b32 s62, s4, 7
	s_and_b32 s60, s60, 0xffffff80
	s_ashr_i32 s63, s62, 31
	s_ashr_i32 s61, s60, 31
	s_lshl_b64 s[64:65], s[62:63], 11
	s_lshl_b64 s[66:67], s[60:61], 11
	s_cmp_eq_u32 s41, 1
	s_cbranch_scc1 .Lgk_pfhead_p19
	s_lshl_b32 s40, s62, 11
	s_add_u32 s20, s14, s40
	s_addc_u32 s21, s15, 0
	s_add_u32 s20, s20, 0x679f000
	s_addc_u32 s21, s21, 0
	s_add_u32 s22, s20, 0x10000
	s_addc_u32 s23, s21, 0
	s_add_u32 s24, s22, 0x10000
	s_addc_u32 s25, s23, 0
	s_add_u32 s26, s24, 0x10000
	s_addc_u32 s27, s25, 0
	s_lshl_b32 s40, s60, 11
	s_add_u32 s28, s14, s40
	s_addc_u32 s29, s15, 0
	s_add_u32 s28, s28, 0x12a0000
	s_addc_u32 s29, s29, 0
	s_add_u32 s30, s28, 0x10000
	s_addc_u32 s31, s29, 0
	s_add_u32 s34, s30, 0x10000
	s_addc_u32 s35, s31, 0
	s_add_u32 s36, s34, 0x10000
	s_addc_u32 s37, s35, 0
	v_readfirstlane_b32 s38, v97
	v_mov_b32_e32 v254, v76
	s_mov_b32 m0, s38
	s_nop 0
	global_load_lds_dwordx4 v254, s[20:21]
	s_add_u32 m0, m0, 0x1000
	s_nop 0
	global_load_lds_dwordx4 v254, s[22:23]
	s_add_u32 m0, m0, 0x1000
	s_nop 0
	global_load_lds_dwordx4 v254, s[24:25]
	s_add_u32 m0, m0, 0x1000
	s_nop 0
	global_load_lds_dwordx4 v254, s[26:27]
	s_add_u32 m0, m0, 0x1000
	s_nop 0
	global_load_lds_dwordx4 v254, s[28:29]
	s_add_u32 m0, m0, 0x1000
	s_nop 0
	global_load_lds_dwordx4 v254, s[30:31]
	s_add_u32 m0, m0, 0x1000
	s_nop 0
	global_load_lds_dwordx4 v254, s[34:35]
	s_add_u32 m0, m0, 0x1000
	s_nop 0
	global_load_lds_dwordx4 v254, s[36:37]
	v_add_u32_e32 v254, 0x80, v254
	s_add_u32 m0, s38, 0x8000
	s_nop 0
	global_load_lds_dwordx4 v254, s[20:21]
	s_add_u32 m0, m0, 0x1000
	s_nop 0
	global_load_lds_dwordx4 v254, s[22:23]
	s_add_u32 m0, m0, 0x1000
	s_nop 0
	global_load_lds_dwordx4 v254, s[24:25]
	s_add_u32 m0, m0, 0x1000
	s_nop 0
	global_load_lds_dwordx4 v254, s[26:27]
	s_add_u32 m0, m0, 0x1000
	s_nop 0
	global_load_lds_dwordx4 v254, s[28:29]
	s_add_u32 m0, m0, 0x1000
	s_nop 0
	global_load_lds_dwordx4 v254, s[30:31]
	s_add_u32 m0, m0, 0x1000
	s_nop 0
	global_load_lds_dwordx4 v254, s[34:35]
	s_add_u32 m0, m0, 0x1000
	s_nop 0
	global_load_lds_dwordx4 v254, s[36:37]
	v_add_u32_e32 v254, 0x80, v254
.Lgk_pfhead_p19:
	v_mov_b32_e32 v48, 0
	v_mov_b32_e32 v49, 0
	v_mov_b32_e32 v50, 0
	v_mov_b32_e32 v51, 0
	v_mov_b32_e32 v52, 0
	v_mov_b32_e32 v53, 0
	v_mov_b32_e32 v54, 0
	v_mov_b32_e32 v55, 0
	v_mov_b32_e32 v56, 0
	v_mov_b32_e32 v57, 0
	v_mov_b32_e32 v58, 0
	v_mov_b32_e32 v59, 0
	v_mov_b32_e32 v60, 0
	v_mov_b32_e32 v61, 0
	v_mov_b32_e32 v62, 0
	v_mov_b32_e32 v63, 0
	v_mov_b32_e32 v32, 0
	v_mov_b32_e32 v33, 0
	v_mov_b32_e32 v34, 0
	v_mov_b32_e32 v35, 0
	v_mov_b32_e32 v36, 0
	v_mov_b32_e32 v37, 0
	v_mov_b32_e32 v38, 0
	v_mov_b32_e32 v39, 0
	v_mov_b32_e32 v40, 0
	v_mov_b32_e32 v41, 0
	v_mov_b32_e32 v42, 0
	v_mov_b32_e32 v43, 0
	v_mov_b32_e32 v44, 0
	v_mov_b32_e32 v45, 0
	v_mov_b32_e32 v46, 0
	v_mov_b32_e32 v47, 0
	v_mov_b32_e32 v16, 0
	v_mov_b32_e32 v17, 0
	v_mov_b32_e32 v18, 0
	v_mov_b32_e32 v19, 0
	v_mov_b32_e32 v20, 0
	v_mov_b32_e32 v21, 0
	v_mov_b32_e32 v22, 0
	v_mov_b32_e32 v23, 0
	v_mov_b32_e32 v24, 0
	v_mov_b32_e32 v25, 0
	v_mov_b32_e32 v26, 0
	v_mov_b32_e32 v27, 0
	v_mov_b32_e32 v28, 0
	v_mov_b32_e32 v29, 0
	v_mov_b32_e32 v30, 0
	v_mov_b32_e32 v31, 0
	v_mov_b32_e32 v0, 0
	v_mov_b32_e32 v1, 0
	v_mov_b32_e32 v2, 0
	v_mov_b32_e32 v3, 0
	v_mov_b32_e32 v4, 0
	v_mov_b32_e32 v5, 0
	v_mov_b32_e32 v6, 0
	v_mov_b32_e32 v7, 0
	v_mov_b32_e32 v8, 0
	v_mov_b32_e32 v9, 0
	v_mov_b32_e32 v10, 0
	v_mov_b32_e32 v11, 0
	v_mov_b32_e32 v12, 0
	v_mov_b32_e32 v13, 0
	v_mov_b32_e32 v14, 0
	v_mov_b32_e32 v15, 0
	s_mov_b32 s39, 7
.Lgk_loop_p19:
	s_waitcnt vmcnt(8)
	s_barrier
	ds_read_b128 v[64:67], v113
	ds_read_b128 v[68:71], v114 offset:16384
	ds_read_b128 v[72:75], v114 offset:20480
	ds_read_b128 v[82:85], v114 offset:24576
	ds_read_b128 v[86:89], v114 offset:28672
	ds_read_b128 v[90:93], v115
	ds_read_b128 v[122:125], v116 offset:16384
	ds_read_b128 v[126:129], v116 offset:20480
	ds_read_b128 v[130:133], v116 offset:24576
	ds_read_b128 v[134:137], v116 offset:28672
	ds_read_b128 v[138:141], v117
	ds_read_b128 v[218:221], v118 offset:16384
	ds_read_b128 v[222:225], v118 offset:20480
	ds_read_b128 v[226:229], v118 offset:24576
	ds_read_b128 v[230:233], v118 offset:28672
	ds_read_b128 v[234:237], v119
	ds_read_b128 v[238:241], v120 offset:16384
	ds_read_b128 v[242:245], v120 offset:20480
	ds_read_b128 v[246:249], v120 offset:24576
	ds_read_b128 v[250:253], v120 offset:28672
	s_waitcnt lgkmcnt(0)
	s_barrier
	s_mov_b32 m0, s38
	s_setprio 1
	v_mfma_f32_32x32x16_bf16 v[48:63], v[64:67], v[68:71], v[48:63]
	v_mfma_f32_32x32x16_bf16 v[32:47], v[64:67], v[72:75], v[32:47]
	global_load_lds_dwordx4 v254, s[20:21]
	s_add_u32 m0, m0, 0x1000
	v_mfma_f32_32x32x16_bf16 v[16:31], v[64:67], v[82:85], v[16:31]
	v_mfma_f32_32x32x16_bf16 v[0:15], v[64:67], v[86:89], v[0:15]
	global_load_lds_dwordx4 v254, s[22:23]
	s_add_u32 m0, m0, 0x1000
	v_mfma_f32_32x32x16_bf16 v[48:63], v[90:93], v[122:125], v[48:63]
	v_mfma_f32_32x32x16_bf16 v[32:47], v[90:93], v[126:129], v[32:47]
	global_load_lds_dwordx4 v254, s[24:25]
	s_add_u32 m0, m0, 0x1000
	v_mfma_f32_32x32x16_bf16 v[16:31], v[90:93], v[130:133], v[16:31]
	v_mfma_f32_32x32x16_bf16 v[0:15], v[90:93], v[134:137], v[0:15]
	global_load_lds_dwordx4 v254, s[26:27]
	s_add_u32 m0, m0, 0x1000
	v_mfma_f32_32x32x16_bf16 v[48:63], v[138:141], v[218:221], v[48:63]
	v_mfma_f32_32x32x16_bf16 v[32:47], v[138:141], v[222:225], v[32:47]
	global_load_lds_dwordx4 v254, s[28:29]
	s_add_u32 m0, m0, 0x1000
	v_mfma_f32_32x32x16_bf16 v[16:31], v[138:141], v[226:229], v[16:31]
	v_mfma_f32_32x32x16_bf16 v[0:15], v[138:141], v[230:233], v[0:15]
	global_load_lds_dwordx4 v254, s[30:31]
	s_add_u32 m0, m0, 0x1000
	v_mfma_f32_32x32x16_bf16 v[48:63], v[234:237], v[238:241], v[48:63]
	v_mfma_f32_32x32x16_bf16 v[32:47], v[234:237], v[242:245], v[32:47]
	global_load_lds_dwordx4 v254, s[34:35]
	s_add_u32 m0, m0, 0x1000
	v_mfma_f32_32x32x16_bf16 v[16:31], v[234:237], v[246:249], v[16:31]
	v_mfma_f32_32x32x16_bf16 v[0:15], v[234:237], v[250:253], v[0:15]
	global_load_lds_dwordx4 v254, s[36:37]
	s_setprio 0
	v_add_u32_e32 v254, 0x80, v254
	s_waitcnt vmcnt(8)
	s_barrier
	ds_read_b128 v[64:67], v113 offset:32768
	ds_read_b128 v[68:71], v114 offset:49152
	ds_read_b128 v[72:75], v114 offset:53248
	ds_read_b128 v[82:85], v114 offset:57344
	ds_read_b128 v[86:89], v114 offset:61440
	ds_read_b128 v[90:93], v115 offset:32768
	ds_read_b128 v[122:125], v116 offset:49152
	ds_read_b128 v[126:129], v116 offset:53248
	ds_read_b128 v[130:133], v116 offset:57344
	ds_read_b128 v[134:137], v116 offset:61440
	ds_read_b128 v[138:141], v117 offset:32768
	ds_read_b128 v[218:221], v118 offset:49152
	ds_read_b128 v[222:225], v118 offset:53248
	ds_read_b128 v[226:229], v118 offset:57344
	ds_read_b128 v[230:233], v118 offset:61440
	ds_read_b128 v[234:237], v119 offset:32768
	ds_read_b128 v[238:241], v120 offset:49152
	ds_read_b128 v[242:245], v120 offset:53248
	ds_read_b128 v[246:249], v120 offset:57344
	ds_read_b128 v[250:253], v120 offset:61440
	s_waitcnt lgkmcnt(0)
	s_barrier
	s_add_u32 m0, s38, 0x8000
	s_setprio 1
	v_mfma_f32_32x32x16_bf16 v[48:63], v[64:67], v[68:71], v[48:63]
	v_mfma_f32_32x32x16_bf16 v[32:47], v[64:67], v[72:75], v[32:47]
	global_load_lds_dwordx4 v254, s[20:21]
	s_add_u32 m0, m0, 0x1000
	v_mfma_f32_32x32x16_bf16 v[16:31], v[64:67], v[82:85], v[16:31]
	v_mfma_f32_32x32x16_bf16 v[0:15], v[64:67], v[86:89], v[0:15]
	global_load_lds_dwordx4 v254, s[22:23]
	s_add_u32 m0, m0, 0x1000
	v_mfma_f32_32x32x16_bf16 v[48:63], v[90:93], v[122:125], v[48:63]
	v_mfma_f32_32x32x16_bf16 v[32:47], v[90:93], v[126:129], v[32:47]
	global_load_lds_dwordx4 v254, s[24:25]
	s_add_u32 m0, m0, 0x1000
	v_mfma_f32_32x32x16_bf16 v[16:31], v[90:93], v[130:133], v[16:31]
	v_mfma_f32_32x32x16_bf16 v[0:15], v[90:93], v[134:137], v[0:15]
	global_load_lds_dwordx4 v254, s[26:27]
	s_add_u32 m0, m0, 0x1000
	v_mfma_f32_32x32x16_bf16 v[48:63], v[138:141], v[218:221], v[48:63]
	v_mfma_f32_32x32x16_bf16 v[32:47], v[138:141], v[222:225], v[32:47]
	global_load_lds_dwordx4 v254, s[28:29]
	s_add_u32 m0, m0, 0x1000
	v_mfma_f32_32x32x16_bf16 v[16:31], v[138:141], v[226:229], v[16:31]
	v_mfma_f32_32x32x16_bf16 v[0:15], v[138:141], v[230:233], v[0:15]
	global_load_lds_dwordx4 v254, s[30:31]
	s_add_u32 m0, m0, 0x1000
	v_mfma_f32_32x32x16_bf16 v[48:63], v[234:237], v[238:241], v[48:63]
	v_mfma_f32_32x32x16_bf16 v[32:47], v[234:237], v[242:245], v[32:47]
	global_load_lds_dwordx4 v254, s[34:35]
	s_add_u32 m0, m0, 0x1000
	v_mfma_f32_32x32x16_bf16 v[16:31], v[234:237], v[246:249], v[16:31]
	v_mfma_f32_32x32x16_bf16 v[0:15], v[234:237], v[250:253], v[0:15]
	global_load_lds_dwordx4 v254, s[36:37]
	s_setprio 0
	v_add_u32_e32 v254, 0x80, v254
	s_sub_u32 s39, s39, 1
	s_cmp_lg_u32 s39, 0
	s_cbranch_scc1 .Lgk_loop_p19
	s_add_u32 s42, s3, s33
	s_cmp_gt_u32 s42, 0x7ff
	s_cbranch_scc1 .Lgk_tailplain_p19
.LBB0_1446_pf_p19:
	s_ashr_i32 s43, s42, 31
	s_lshr_b32 s43, s43, 25
	s_add_i32 s43, s42, s43
	s_ashr_i32 s44, s43, 7
	s_and_b32 s43, s43, 0xffffff80
	s_sub_i32 s52, s42, s43
	s_ashr_i32 s43, s52, 31
	s_lshr_b32 s43, s43, 29
	s_add_i32 s45, s52, s43
	s_and_b32 s43, s45, -8
	s_lshl_b32 s44, s44, 3
	s_sub_i32 s43, s52, s43
	s_add_i32 s43, s43, s44
	s_lshl_b32 s44, s45, 4
	s_lshl_b32 s46, s43, 7
	s_and_b32 s44, s44, 0xffffff80
	s_ashr_i32 s47, s46, 31
	s_ashr_i32 s45, s44, 31
	s_lshl_b64 s[48:49], s[46:47], 11
	s_lshl_b64 s[50:51], s[44:45], 11
	s_lshl_b32 s40, s46, 11
	s_add_u32 s20, s14, s40
	s_addc_u32 s21, s15, 0
	s_add_u32 s20, s20, 0x679f000
	s_addc_u32 s21, s21, 0
	s_add_u32 s22, s20, 0x10000
	s_addc_u32 s23, s21, 0
	s_add_u32 s24, s22, 0x10000
	s_addc_u32 s25, s23, 0
	s_add_u32 s26, s24, 0x10000
	s_addc_u32 s27, s25, 0
	s_lshl_b32 s40, s44, 11
	s_add_u32 s28, s14, s40
	s_addc_u32 s29, s15, 0
	s_add_u32 s28, s28, 0x12a0000
	s_addc_u32 s29, s29, 0
	s_add_u32 s30, s28, 0x10000
	s_addc_u32 s31, s29, 0
	s_add_u32 s34, s30, 0x10000
	s_addc_u32 s35, s31, 0
	s_add_u32 s36, s34, 0x10000
	s_addc_u32 s37, s35, 0
	v_mov_b32_e32 v254, v76
	s_mov_b32 s41, 1
	s_waitcnt vmcnt(8)
	s_barrier
	ds_read_b128 v[64:67], v113
	ds_read_b128 v[68:71], v114 offset:16384
	ds_read_b128 v[72:75], v114 offset:20480
	ds_read_b128 v[82:85], v114 offset:24576
	ds_read_b128 v[86:89], v114 offset:28672
	ds_read_b128 v[90:93], v115
	ds_read_b128 v[122:125], v116 offset:16384
	ds_read_b128 v[126:129], v116 offset:20480
	ds_read_b128 v[130:133], v116 offset:24576
	ds_read_b128 v[134:137], v116 offset:28672
	ds_read_b128 v[138:141], v117
	ds_read_b128 v[218:221], v118 offset:16384
	ds_read_b128 v[222:225], v118 offset:20480
	ds_read_b128 v[226:229], v118 offset:24576
	ds_read_b128 v[230:233], v118 offset:28672
	ds_read_b128 v[234:237], v119
	ds_read_b128 v[238:241], v120 offset:16384
	ds_read_b128 v[242:245], v120 offset:20480
	ds_read_b128 v[246:249], v120 offset:24576
	ds_read_b128 v[250:253], v120 offset:28672
	s_waitcnt lgkmcnt(0)
	s_barrier
	s_mov_b32 m0, s38
	s_setprio 1
	v_mfma_f32_32x32x16_bf16 v[48:63], v[64:67], v[68:71], v[48:63]
	v_mfma_f32_32x32x16_bf16 v[32:47], v[64:67], v[72:75], v[32:47]
	global_load_lds_dwordx4 v254, s[20:21]
	s_add_u32 m0, m0, 0x1000
	v_mfma_f32_32x32x16_bf16 v[16:31], v[64:67], v[82:85], v[16:31]
	v_mfma_f32_32x32x16_bf16 v[0:15], v[64:67], v[86:89], v[0:15]
	global_load_lds_dwordx4 v254, s[22:23]
	s_add_u32 m0, m0, 0x1000
	v_mfma_f32_32x32x16_bf16 v[48:63], v[90:93], v[122:125], v[48:63]
	v_mfma_f32_32x32x16_bf16 v[32:47], v[90:93], v[126:129], v[32:47]
	global_load_lds_dwordx4 v254, s[24:25]
	s_add_u32 m0, m0, 0x1000
	v_mfma_f32_32x32x16_bf16 v[16:31], v[90:93], v[130:133], v[16:31]
	v_mfma_f32_32x32x16_bf16 v[0:15], v[90:93], v[134:137], v[0:15]
	global_load_lds_dwordx4 v254, s[26:27]
	s_add_u32 m0, m0, 0x1000
	v_mfma_f32_32x32x16_bf16 v[48:63], v[138:141], v[218:221], v[48:63]
	v_mfma_f32_32x32x16_bf16 v[32:47], v[138:141], v[222:225], v[32:47]
	global_load_lds_dwordx4 v254, s[28:29]
	s_add_u32 m0, m0, 0x1000
	v_mfma_f32_32x32x16_bf16 v[16:31], v[138:141], v[226:229], v[16:31]
	v_mfma_f32_32x32x16_bf16 v[0:15], v[138:141], v[230:233], v[0:15]
	global_load_lds_dwordx4 v254, s[30:31]
	s_add_u32 m0, m0, 0x1000
	v_mfma_f32_32x32x16_bf16 v[48:63], v[234:237], v[238:241], v[48:63]
	v_mfma_f32_32x32x16_bf16 v[32:47], v[234:237], v[242:245], v[32:47]
	global_load_lds_dwordx4 v254, s[34:35]
	s_add_u32 m0, m0, 0x1000
	v_mfma_f32_32x32x16_bf16 v[16:31], v[234:237], v[246:249], v[16:31]
	v_mfma_f32_32x32x16_bf16 v[0:15], v[234:237], v[250:253], v[0:15]
	global_load_lds_dwordx4 v254, s[36:37]
	s_setprio 0
	v_add_u32_e32 v254, 0x80, v254
	s_waitcnt vmcnt(8)
	s_barrier
	ds_read_b128 v[64:67], v113 offset:32768
	ds_read_b128 v[68:71], v114 offset:49152
	ds_read_b128 v[72:75], v114 offset:53248
	ds_read_b128 v[82:85], v114 offset:57344
	ds_read_b128 v[86:89], v114 offset:61440
	ds_read_b128 v[90:93], v115 offset:32768
	ds_read_b128 v[122:125], v116 offset:49152
	ds_read_b128 v[126:129], v116 offset:53248
	ds_read_b128 v[130:133], v116 offset:57344
	ds_read_b128 v[134:137], v116 offset:61440
	ds_read_b128 v[138:141], v117 offset:32768
	ds_read_b128 v[218:221], v118 offset:49152
	ds_read_b128 v[222:225], v118 offset:53248
	ds_read_b128 v[226:229], v118 offset:57344
	ds_read_b128 v[230:233], v118 offset:61440
	ds_read_b128 v[234:237], v119 offset:32768
	ds_read_b128 v[238:241], v120 offset:49152
	ds_read_b128 v[242:245], v120 offset:53248
	ds_read_b128 v[246:249], v120 offset:57344
	ds_read_b128 v[250:253], v120 offset:61440
	s_waitcnt lgkmcnt(0)
	s_barrier
	s_add_u32 m0, s38, 0x8000
	s_setprio 1
	v_mfma_f32_32x32x16_bf16 v[48:63], v[64:67], v[68:71], v[48:63]
	v_mfma_f32_32x32x16_bf16 v[32:47], v[64:67], v[72:75], v[32:47]
	global_load_lds_dwordx4 v254, s[20:21]
	s_add_u32 m0, m0, 0x1000
	v_mfma_f32_32x32x16_bf16 v[16:31], v[64:67], v[82:85], v[16:31]
	v_mfma_f32_32x32x16_bf16 v[0:15], v[64:67], v[86:89], v[0:15]
	global_load_lds_dwordx4 v254, s[22:23]
	s_add_u32 m0, m0, 0x1000
	v_mfma_f32_32x32x16_bf16 v[48:63], v[90:93], v[122:125], v[48:63]
	v_mfma_f32_32x32x16_bf16 v[32:47], v[90:93], v[126:129], v[32:47]
	global_load_lds_dwordx4 v254, s[24:25]
	s_add_u32 m0, m0, 0x1000
	v_mfma_f32_32x32x16_bf16 v[16:31], v[90:93], v[130:133], v[16:31]
	v_mfma_f32_32x32x16_bf16 v[0:15], v[90:93], v[134:137], v[0:15]
	global_load_lds_dwordx4 v254, s[26:27]
	s_add_u32 m0, m0, 0x1000
	v_mfma_f32_32x32x16_bf16 v[48:63], v[138:141], v[218:221], v[48:63]
	v_mfma_f32_32x32x16_bf16 v[32:47], v[138:141], v[222:225], v[32:47]
	global_load_lds_dwordx4 v254, s[28:29]
	s_add_u32 m0, m0, 0x1000
	v_mfma_f32_32x32x16_bf16 v[16:31], v[138:141], v[226:229], v[16:31]
	v_mfma_f32_32x32x16_bf16 v[0:15], v[138:141], v[230:233], v[0:15]
	global_load_lds_dwordx4 v254, s[30:31]
	s_add_u32 m0, m0, 0x1000
	v_mfma_f32_32x32x16_bf16 v[48:63], v[234:237], v[238:241], v[48:63]
	v_mfma_f32_32x32x16_bf16 v[32:47], v[234:237], v[242:245], v[32:47]
	global_load_lds_dwordx4 v254, s[34:35]
	s_add_u32 m0, m0, 0x1000
	v_mfma_f32_32x32x16_bf16 v[16:31], v[234:237], v[246:249], v[16:31]
	v_mfma_f32_32x32x16_bf16 v[0:15], v[234:237], v[250:253], v[0:15]
	global_load_lds_dwordx4 v254, s[36:37]
	s_setprio 0
	v_add_u32_e32 v254, 0x80, v254
	s_branch .LBB0_1450
.Lgk_tailplain_p19:
	s_mov_b32 s41, 0
	s_waitcnt vmcnt(8)
	s_barrier
	ds_read_b128 v[64:67], v113
	ds_read_b128 v[68:71], v114 offset:16384
	ds_read_b128 v[72:75], v114 offset:20480
	ds_read_b128 v[82:85], v114 offset:24576
	ds_read_b128 v[86:89], v114 offset:28672
	ds_read_b128 v[90:93], v115
	ds_read_b128 v[122:125], v116 offset:16384
	ds_read_b128 v[126:129], v116 offset:20480
	ds_read_b128 v[130:133], v116 offset:24576
	ds_read_b128 v[134:137], v116 offset:28672
	ds_read_b128 v[138:141], v117
	ds_read_b128 v[218:221], v118 offset:16384
	ds_read_b128 v[222:225], v118 offset:20480
	ds_read_b128 v[226:229], v118 offset:24576
	ds_read_b128 v[230:233], v118 offset:28672
	ds_read_b128 v[234:237], v119
	ds_read_b128 v[238:241], v120 offset:16384
	ds_read_b128 v[242:245], v120 offset:20480
	ds_read_b128 v[246:249], v120 offset:24576
	ds_read_b128 v[250:253], v120 offset:28672
	s_waitcnt lgkmcnt(0)
	s_barrier
	s_setprio 1
	v_mfma_f32_32x32x16_bf16 v[48:63], v[64:67], v[68:71], v[48:63]
	v_mfma_f32_32x32x16_bf16 v[32:47], v[64:67], v[72:75], v[32:47]
	v_mfma_f32_32x32x16_bf16 v[16:31], v[64:67], v[82:85], v[16:31]
	v_mfma_f32_32x32x16_bf16 v[0:15], v[64:67], v[86:89], v[0:15]
	v_mfma_f32_32x32x16_bf16 v[48:63], v[90:93], v[122:125], v[48:63]
	v_mfma_f32_32x32x16_bf16 v[32:47], v[90:93], v[126:129], v[32:47]
	v_mfma_f32_32x32x16_bf16 v[16:31], v[90:93], v[130:133], v[16:31]
	v_mfma_f32_32x32x16_bf16 v[0:15], v[90:93], v[134:137], v[0:15]
	v_mfma_f32_32x32x16_bf16 v[48:63], v[138:141], v[218:221], v[48:63]
	v_mfma_f32_32x32x16_bf16 v[32:47], v[138:141], v[222:225], v[32:47]
	v_mfma_f32_32x32x16_bf16 v[16:31], v[138:141], v[226:229], v[16:31]
	v_mfma_f32_32x32x16_bf16 v[0:15], v[138:141], v[230:233], v[0:15]
	v_mfma_f32_32x32x16_bf16 v[48:63], v[234:237], v[238:241], v[48:63]
	v_mfma_f32_32x32x16_bf16 v[32:47], v[234:237], v[242:245], v[32:47]
	v_mfma_f32_32x32x16_bf16 v[16:31], v[234:237], v[246:249], v[16:31]
	v_mfma_f32_32x32x16_bf16 v[0:15], v[234:237], v[250:253], v[0:15]
	s_setprio 0
	s_waitcnt vmcnt(0)
	s_barrier
	ds_read_b128 v[64:67], v113 offset:32768
	ds_read_b128 v[68:71], v114 offset:49152
	ds_read_b128 v[72:75], v114 offset:53248
	ds_read_b128 v[82:85], v114 offset:57344
	ds_read_b128 v[86:89], v114 offset:61440
	ds_read_b128 v[90:93], v115 offset:32768
	ds_read_b128 v[122:125], v116 offset:49152
	ds_read_b128 v[126:129], v116 offset:53248
	ds_read_b128 v[130:133], v116 offset:57344
	ds_read_b128 v[134:137], v116 offset:61440
	ds_read_b128 v[138:141], v117 offset:32768
	ds_read_b128 v[218:221], v118 offset:49152
	ds_read_b128 v[222:225], v118 offset:53248
	ds_read_b128 v[226:229], v118 offset:57344
	ds_read_b128 v[230:233], v118 offset:61440
	ds_read_b128 v[234:237], v119 offset:32768
	ds_read_b128 v[238:241], v120 offset:49152
	ds_read_b128 v[242:245], v120 offset:53248
	ds_read_b128 v[246:249], v120 offset:57344
	ds_read_b128 v[250:253], v120 offset:61440
	s_waitcnt lgkmcnt(0)
	s_barrier
	s_setprio 1
	v_mfma_f32_32x32x16_bf16 v[48:63], v[64:67], v[68:71], v[48:63]
	v_mfma_f32_32x32x16_bf16 v[32:47], v[64:67], v[72:75], v[32:47]
	v_mfma_f32_32x32x16_bf16 v[16:31], v[64:67], v[82:85], v[16:31]
	v_mfma_f32_32x32x16_bf16 v[0:15], v[64:67], v[86:89], v[0:15]
	v_mfma_f32_32x32x16_bf16 v[48:63], v[90:93], v[122:125], v[48:63]
	v_mfma_f32_32x32x16_bf16 v[32:47], v[90:93], v[126:129], v[32:47]
	v_mfma_f32_32x32x16_bf16 v[16:31], v[90:93], v[130:133], v[16:31]
	v_mfma_f32_32x32x16_bf16 v[0:15], v[90:93], v[134:137], v[0:15]
	v_mfma_f32_32x32x16_bf16 v[48:63], v[138:141], v[218:221], v[48:63]
	v_mfma_f32_32x32x16_bf16 v[32:47], v[138:141], v[222:225], v[32:47]
	v_mfma_f32_32x32x16_bf16 v[16:31], v[138:141], v[226:229], v[16:31]
	v_mfma_f32_32x32x16_bf16 v[0:15], v[138:141], v[230:233], v[0:15]
	v_mfma_f32_32x32x16_bf16 v[48:63], v[234:237], v[238:241], v[48:63]
	v_mfma_f32_32x32x16_bf16 v[32:47], v[234:237], v[242:245], v[32:47]
	v_mfma_f32_32x32x16_bf16 v[16:31], v[234:237], v[246:249], v[16:31]
	v_mfma_f32_32x32x16_bf16 v[0:15], v[234:237], v[250:253], v[0:15]
	s_setprio 0
	s_branch .LBB0_1450
.LBB0_1450:
	v_add_u32_e32 v82, s62, v95
	v_ashrrev_i32_e32 v83, 31, v82
	v_lshl_add_u64 v[64:65], v[82:83], 2, s[6:7]
	v_add_co_u32_e32 v66, vcc, s70, v64
	v_or_b32_e32 v84, 8, v82
	s_nop 0
	v_addc_co_u32_e32 v67, vcc, 0, v65, vcc
	global_load_dwordx4 v[86:89], v[64:65], off
	global_load_dwordx4 v[90:93], v[66:67], off
	v_add_co_u32_e32 v66, vcc, s71, v64
	v_ashrrev_i32_e32 v85, 31, v84
	s_nop 0
	v_addc_co_u32_e32 v67, vcc, 0, v65, vcc
	v_add_co_u32_e32 v68, vcc, s72, v64
	v_lshl_add_u64 v[144:145], v[84:85], 2, s[6:7]
	s_nop 0
	v_addc_co_u32_e32 v69, vcc, 0, v65, vcc
	global_load_dwordx4 v[128:131], v[66:67], off
	global_load_dwordx4 v[132:135], v[68:69], off
	v_add_co_u32_e32 v66, vcc, s73, v64
	s_add_i32 s61, s62, 0xffffe000
	s_nop 0
	v_addc_co_u32_e32 v67, vcc, 0, v65, vcc
	v_add_co_u32_e32 v68, vcc, s74, v64
	s_lshr_b32 s61, s61, 12
	s_nop 0
	v_addc_co_u32_e32 v69, vcc, 0, v65, vcc
	global_load_dwordx4 v[136:139], v[66:67], off
	global_load_dwordx4 v[140:143], v[68:69], off
	v_add_co_u32_e32 v66, vcc, s75, v64
	s_mulk_i32 s61, 0xc00
	s_nop 0
	v_addc_co_u32_e32 v67, vcc, 0, v65, vcc
	v_add_co_u32_e32 v68, vcc, s76, v64
	s_addk_i32 s61, 0xc00
	s_nop 0
	v_addc_co_u32_e32 v69, vcc, 0, v65, vcc
	global_load_dwordx4 v[64:67], v[66:67], off
	s_nop 0
	global_load_dwordx4 v[68:71], v[68:69], off
	v_add_co_u32_e32 v72, vcc, s70, v144
	s_cmp_gt_i32 s4, 63
	s_nop 0
	v_addc_co_u32_e32 v73, vcc, 0, v145, vcc
	v_add_co_u32_e32 v146, vcc, s71, v144
	global_load_dword v83, v[144:145], off
	s_nop 0
	global_load_dwordx4 v[72:75], v[72:73], off
	v_addc_co_u32_e32 v147, vcc, 0, v145, vcc
	s_cselect_b32 s4, s61, 0
	s_lshl_b64 s[62:63], s[4:5], 2
	s_add_u32 s62, s10, s62
	s_addc_u32 s63, s11, s63
	v_or_b32_e32 v123, 1, v82
	v_or_b32_e32 v125, 2, v82
	v_or_b32_e32 v127, 3, v82
	s_cmp_gt_i32 s77, 63
	s_waitcnt vmcnt(0)
	v_add_f32_e32 v85, v86, v90
	v_add_f32_e32 v86, v87, v91
	v_add_f32_e32 v87, v88, v92
	v_add_f32_e32 v88, v89, v93
	v_add_f32_e32 v92, v131, v135
	v_add_f32_e32 v89, v128, v132
	v_add_f32_e32 v122, v88, v92
	v_add_f32_e32 v90, v129, v133
	v_add_f32_e32 v85, v85, v89
	v_add_f32_e32 v86, v86, v90
	v_add_f32_e32 v91, v130, v134
	v_add_f32_e32 v87, v87, v91
	v_add_f32_e32 v88, v136, v140
	v_add_f32_e32 v89, v137, v141
	v_add_f32_e32 v90, v138, v142
	v_add_f32_e32 v124, v139, v143
	v_add_f32_e32 v64, v64, v68
	v_add_f32_e32 v65, v65, v69
	v_add_f32_e32 v64, v88, v64
	v_add_f32_e32 v65, v89, v65
	v_add_f32_e32 v85, v85, v64
	v_add_co_u32_e32 v64, vcc, s72, v144
	v_add_f32_e32 v126, v86, v65
	s_nop 0
	v_addc_co_u32_e32 v65, vcc, 0, v145, vcc
	global_load_dwordx4 v[128:131], v[146:147], off
	global_load_dwordx4 v[132:135], v[64:65], off
	v_add_co_u32_e32 v64, vcc, s73, v144
	v_add_f32_e32 v66, v66, v70
	s_nop 0
	v_addc_co_u32_e32 v65, vcc, 0, v145, vcc
	v_add_co_u32_e32 v68, vcc, s74, v144
	v_add_f32_e32 v66, v90, v66
	s_nop 0
	v_addc_co_u32_e32 v69, vcc, 0, v145, vcc
	global_load_dwordx4 v[136:139], v[64:65], off
	global_load_dwordx4 v[140:143], v[68:69], off
	v_add_co_u32_e32 v64, vcc, s75, v144
	v_or_b32_e32 v86, 16, v82
	s_nop 0
	v_addc_co_u32_e32 v65, vcc, 0, v145, vcc
	v_add_f32_e32 v217, v87, v66
	v_add_co_u32_e32 v68, vcc, s76, v144
	v_ashrrev_i32_e32 v87, 31, v86
	s_nop 0
	v_addc_co_u32_e32 v69, vcc, 0, v145, vcc
	v_lshl_add_u64 v[88:89], v[86:87], 2, s[6:7]
	v_add_co_u32_e32 v90, vcc, s70, v88
	global_load_dwordx4 v[144:147], v[64:65], off
	global_load_dwordx4 v[148:151], v[68:69], off
	v_or_b32_e32 v68, 9, v82
	v_addc_co_u32_e32 v91, vcc, 0, v89, vcc
	v_ashrrev_i32_e32 v69, 31, v68
	v_add_co_u32_e32 v92, vcc, s71, v88
	v_lshl_add_u64 v[64:65], v[68:69], 2, s[6:7]
	s_nop 0
	v_addc_co_u32_e32 v93, vcc, 0, v89, vcc
	global_load_dwordx3 v[64:66], v[64:65], off
	s_nop 0
	global_load_dword v69, v[88:89], off
	global_load_dwordx4 v[152:155], v[90:91], off
	global_load_dwordx4 v[156:159], v[92:93], off
	v_add_co_u32_e32 v90, vcc, s72, v88
	v_add_f32_e32 v67, v67, v71
	s_nop 0
	v_addc_co_u32_e32 v91, vcc, 0, v89, vcc
	v_add_co_u32_e32 v92, vcc, s73, v88
	v_add_f32_e32 v67, v124, v67
	s_nop 0
	v_addc_co_u32_e32 v93, vcc, 0, v89, vcc
	global_load_dwordx4 v[160:163], v[90:91], off
	global_load_dwordx4 v[164:167], v[92:93], off
	v_add_co_u32_e32 v90, vcc, s74, v88
	v_fmamk_f32 v85, v85, 0x3a800000, v121
	s_nop 0
	v_addc_co_u32_e32 v91, vcc, 0, v89, vcc
	v_add_co_u32_e32 v92, vcc, s75, v88
	s_waitcnt vmcnt(10)
	v_add_f32_e32 v70, v128, v132
	v_addc_co_u32_e32 v93, vcc, 0, v89, vcc
	global_load_dwordx4 v[168:171], v[90:91], off
	global_load_dwordx4 v[172:175], v[92:93], off
	v_add_co_u32_e32 v90, vcc, s76, v88
	v_or_b32_e32 v88, 17, v82
	s_nop 0
	v_addc_co_u32_e32 v91, vcc, 0, v89, vcc
	v_ashrrev_i32_e32 v89, 31, v88
	v_lshl_add_u64 v[92:93], v[88:89], 2, s[6:7]
	global_load_dwordx4 v[176:179], v[90:91], off
	global_load_dwordx3 v[196:198], v[92:93], off
	v_or_b32_e32 v90, 24, v82
	v_ashrrev_i32_e32 v91, 31, v90
	v_lshl_add_u64 v[92:93], v[90:91], 2, s[6:7]
	v_add_co_u32_e32 v180, vcc, s70, v92
	v_add_f32_e32 v89, v122, v67
	s_nop 0
	v_addc_co_u32_e32 v181, vcc, 0, v93, vcc
	v_add_co_u32_e32 v184, vcc, s71, v92
	global_load_dword v87, v[92:93], off
	s_nop 0
	global_load_dwordx4 v[180:183], v[180:181], off
	v_addc_co_u32_e32 v185, vcc, 0, v93, vcc
	v_add_co_u32_e32 v188, vcc, s72, v92
	v_add_f32_e32 v67, v83, v72
	s_nop 0
	v_addc_co_u32_e32 v189, vcc, 0, v93, vcc
	v_add_co_u32_e32 v192, vcc, s73, v92
	global_load_dwordx4 v[184:187], v[184:185], off
	s_nop 0
	global_load_dwordx4 v[188:191], v[188:189], off
	v_addc_co_u32_e32 v193, vcc, 0, v93, vcc
	v_add_co_u32_e32 v202, vcc, s74, v92
	v_add_f32_e32 v67, v67, v70
	s_nop 0
	v_addc_co_u32_e32 v203, vcc, 0, v93, vcc
	v_add_co_u32_e32 v206, vcc, s75, v92
	global_load_dwordx4 v[192:195], v[192:193], off
	s_nop 0
	global_load_dwordx4 v[202:205], v[202:203], off
	v_addc_co_u32_e32 v207, vcc, 0, v93, vcc
	v_add_co_u32_e32 v92, vcc, s76, v92
	s_waitcnt vmcnt(18)
	v_add_f32_e32 v70, v136, v140
	v_addc_co_u32_e32 v93, vcc, 0, v93, vcc
	global_load_dwordx4 v[206:209], v[206:207], off
	s_nop 0
	global_load_dwordx4 v[210:213], v[92:93], off
	v_or_b32_e32 v92, 25, v82
	v_ashrrev_i32_e32 v93, 31, v92
	v_lshl_add_u64 v[214:215], v[92:93], 2, s[6:7]
	global_load_dwordx3 v[214:216], v[214:215], off
	s_waitcnt vmcnt(19)
	v_add_f32_e32 v71, v144, v148
	v_add_f32_e32 v70, v70, v71
	v_add_f32_e32 v72, v67, v70
	s_waitcnt vmcnt(18)
	v_add_f32_e32 v64, v64, v73
	v_add_f32_e32 v67, v129, v133
	v_add_f32_e32 v64, v64, v67
	v_add_f32_e32 v67, v137, v141
	v_add_f32_e32 v70, v145, v149
	v_add_f32_e32 v67, v67, v70
	v_add_f32_e32 v73, v64, v67
	v_add_f32_e32 v64, v65, v74
	v_add_f32_e32 v65, v130, v134
	v_add_f32_e32 v64, v64, v65
	v_add_f32_e32 v65, v138, v142
	v_add_f32_e32 v67, v146, v150
	v_add_f32_e32 v65, v65, v67
	v_add_f32_e32 v74, v64, v65
	v_add_f32_e32 v64, v66, v75
	v_add_f32_e32 v65, v131, v135
	v_add_f32_e32 v64, v64, v65
	v_add_f32_e32 v65, v139, v143
	v_add_f32_e32 v66, v147, v151
	v_add_f32_e32 v65, v65, v66
	v_add_f32_e32 v75, v64, v65
	s_waitcnt vmcnt(16)
	v_add_f32_e32 v64, v69, v152
	s_waitcnt vmcnt(14)
	v_add_f32_e32 v65, v156, v160
	v_add_f32_e32 v64, v64, v65
	s_waitcnt vmcnt(12)
	v_add_f32_e32 v65, v164, v168
	v_or_b32_e32 v129, 10, v82
	v_or_b32_e32 v130, 11, v82
	v_or_b32_e32 v131, 18, v82
	v_or_b32_e32 v132, 19, v82
	v_or_b32_e32 v133, 26, v82
	s_waitcnt vmcnt(10)
	v_add_f32_e32 v66, v172, v176
	v_add_f32_e32 v65, v65, v66
	v_add_f32_e32 v83, v64, v65
	s_waitcnt vmcnt(9)
	v_add_f32_e32 v64, v196, v153
	v_add_f32_e32 v65, v157, v161
	v_add_f32_e32 v64, v64, v65
	v_add_f32_e32 v65, v165, v169
	v_add_f32_e32 v66, v173, v177
	v_add_f32_e32 v65, v65, v66
	v_add_f32_e32 v91, v64, v65
	v_or_b32_e32 v64, s60, v94
	v_ashrrev_i32_e32 v65, 31, v64
	v_add_f32_e32 v66, v197, v154
	v_lshl_add_u64 v[70:71], v[64:65], 2, s[62:63]
	v_add_f32_e32 v65, v158, v162
	v_add_f32_e32 v65, v66, v65
	v_add_f32_e32 v66, v166, v170
	v_add_f32_e32 v67, v174, v178
	v_add_f32_e32 v66, v66, v67
	v_add_f32_e32 v93, v65, v66
	v_add_f32_e32 v65, v198, v155
	v_add_f32_e32 v66, v159, v163
	v_add_f32_e32 v65, v65, v66
	v_add_f32_e32 v66, v167, v171
	v_add_f32_e32 v67, v175, v179
	v_add_f32_e32 v66, v66, v67
	v_add_f32_e32 v122, v65, v66
	s_waitcnt vmcnt(7)
	v_add_f32_e32 v65, v87, v180
	s_waitcnt vmcnt(5)
	v_add_f32_e32 v66, v184, v188
	v_add_f32_e32 v65, v65, v66
	v_add_f32_e32 v124, v185, v189
	v_add_f32_e32 v135, v187, v191
	s_waitcnt vmcnt(3)
	v_add_f32_e32 v66, v192, v202
	global_load_dword v69, v[70:71], off
	global_load_dword v67, v[70:71], off offset:128
	s_mov_b64 s[62:63], -1
	s_waitcnt vmcnt(3)
	v_add_f32_e32 v87, v206, v210
	v_add_f32_e32 v66, v66, v87
	v_add_f32_e32 v87, v65, v66
	v_add_f32_e32 v128, v207, v211
	s_waitcnt vmcnt(2)
	v_add_f32_e32 v65, v214, v181
	v_add_f32_e32 v65, v65, v124
	v_add_f32_e32 v124, v193, v203
	v_add_f32_e32 v124, v124, v128
	v_add_f32_e32 v124, v65, v124
	v_add_f32_e32 v65, v215, v182
	v_add_f32_e32 v128, v186, v190
	v_add_f32_e32 v65, v65, v128
	v_add_f32_e32 v128, v194, v204
	v_add_f32_e32 v134, v208, v212
	v_add_f32_e32 v128, v128, v134
	v_add_f32_e32 v128, v65, v128
	v_add_f32_e32 v65, v216, v183
	v_add_f32_e32 v65, v65, v135
	v_add_f32_e32 v135, v195, v205
	v_add_f32_e32 v136, v209, v213
	v_add_f32_e32 v135, v135, v136
	global_load_dword v66, v[70:71], off offset:256
	v_add_f32_e32 v135, v65, v135
	global_load_dword v65, v[70:71], off offset:384
	v_fmamk_f32 v70, v126, 0x3a800000, v121
	v_rsq_f32_e32 v137, v70
	v_fmamk_f32 v70, v217, 0x3a800000, v121
	v_rsq_f32_e32 v138, v70
	v_fmamk_f32 v70, v89, 0x3a800000, v121
	v_rsq_f32_e32 v139, v70
	v_fmamk_f32 v70, v72, 0x3a800000, v121
	v_rsq_f32_e32 v140, v70
	v_fmamk_f32 v70, v73, 0x3a800000, v121
	v_rsq_f32_e32 v141, v70
	v_fmamk_f32 v70, v74, 0x3a800000, v121
	v_rsq_f32_e32 v142, v70
	v_fmamk_f32 v70, v75, 0x3a800000, v121
	v_rsq_f32_e32 v143, v70
	v_fmamk_f32 v70, v83, 0x3a800000, v121
	v_rsq_f32_e32 v144, v70
	v_fmamk_f32 v70, v91, 0x3a800000, v121
	v_rsq_f32_e32 v145, v70
	v_fmamk_f32 v70, v93, 0x3a800000, v121
	v_rsq_f32_e32 v146, v70
	v_fmamk_f32 v70, v122, 0x3a800000, v121
	v_rsq_f32_e32 v147, v70
	v_fmamk_f32 v70, v87, 0x3a800000, v121
	v_rsq_f32_e32 v148, v70
	v_fmamk_f32 v70, v124, 0x3a800000, v121
	v_rsq_f32_e32 v149, v70
	v_fmamk_f32 v70, v128, 0x3a800000, v121
	v_rsq_f32_e32 v150, v70
	v_fmamk_f32 v70, v135, 0x3a800000, v121
	v_rsq_f32_e32 v136, v85
	v_rsq_f32_e32 v128, v70
	v_or_b32_e32 v134, 27, v82
	s_waitcnt vmcnt(3)
	v_fma_f32 v126, v48, v136, v69
	v_fma_f32 v124, v49, v137, v69
	v_fma_f32 v122, v50, v138, v69
	v_fma_f32 v93, v51, v139, v69
	v_fma_f32 v91, v52, v140, v69
	v_fma_f32 v89, v53, v141, v69
	v_fma_f32 v87, v54, v142, v69
	v_fma_f32 v85, v55, v143, v69
	v_fma_f32 v83, v56, v144, v69
	v_fma_f32 v75, v57, v145, v69
	v_fma_f32 v74, v58, v146, v69
	v_fma_f32 v73, v59, v147, v69
	v_fma_f32 v72, v60, v148, v69
	v_fma_f32 v71, v61, v149, v69
	v_fma_f32 v70, v62, v150, v69
	v_fmac_f32_e32 v69, v63, v128
	s_waitcnt vmcnt(2)
	v_fma_f32 v62, v32, v136, v67
	v_fma_f32 v61, v33, v137, v67
	v_fma_f32 v60, v34, v138, v67
	v_fma_f32 v59, v35, v139, v67
	v_fma_f32 v58, v36, v140, v67
	v_fma_f32 v57, v37, v141, v67
	v_fma_f32 v56, v38, v142, v67
	v_fma_f32 v55, v39, v143, v67
	v_fma_f32 v54, v40, v144, v67
	v_fma_f32 v53, v41, v145, v67
	v_fma_f32 v52, v42, v146, v67
	v_fma_f32 v51, v43, v147, v67
	v_fma_f32 v50, v44, v148, v67
	v_fma_f32 v49, v45, v149, v67
	v_fma_f32 v48, v46, v150, v67
	v_fmac_f32_e32 v67, v47, v128
	s_waitcnt vmcnt(1)
	v_fma_f32 v47, v16, v136, v66
	v_fma_f32 v46, v17, v137, v66
	v_fma_f32 v45, v18, v138, v66
	v_fma_f32 v44, v19, v139, v66
	v_fma_f32 v43, v20, v140, v66
	v_fma_f32 v42, v21, v141, v66
	v_fma_f32 v41, v22, v142, v66
	v_fma_f32 v40, v23, v143, v66
	v_fma_f32 v39, v24, v144, v66
	v_fma_f32 v38, v25, v145, v66
	v_fma_f32 v37, v26, v146, v66
	v_fma_f32 v36, v27, v147, v66
	v_fma_f32 v35, v28, v148, v66
	v_fma_f32 v34, v29, v149, v66
	v_fma_f32 v33, v30, v150, v66
	v_fmac_f32_e32 v66, v31, v128
	s_waitcnt vmcnt(0)
	v_fma_f32 v30, v0, v136, v65
	v_fma_f32 v29, v1, v137, v65
	v_fma_f32 v26, v2, v138, v65
	v_fma_f32 v25, v3, v139, v65
	v_fma_f32 v22, v4, v140, v65
	v_fma_f32 v21, v5, v141, v65
	v_fma_f32 v19, v6, v142, v65
	v_fma_f32 v18, v7, v143, v65
	v_fma_f32 v17, v8, v144, v65
	v_fma_f32 v16, v9, v145, v65
	v_fma_f32 v9, v10, v146, v65
	v_fma_f32 v8, v11, v147, v65
	v_fma_f32 v5, v12, v148, v65
	v_fma_f32 v4, v13, v149, v65
	v_fma_f32 v1, v14, v150, v65
	v_lshlrev_b32_e32 v32, 10, v82
	v_lshlrev_b32_e32 v31, 10, v123
	v_lshlrev_b32_e32 v28, 10, v125
	v_lshlrev_b32_e32 v27, 10, v127
	v_lshlrev_b32_e32 v24, 10, v84
	v_lshlrev_b32_e32 v23, 10, v68
	v_lshlrev_b32_e32 v20, 10, v129
	v_lshlrev_b32_e32 v14, 10, v130
	v_lshlrev_b32_e32 v13, 10, v86
	v_lshlrev_b32_e32 v12, 10, v88
	v_lshlrev_b32_e32 v11, 10, v131
	v_lshlrev_b32_e32 v10, 10, v132
	v_lshlrev_b32_e32 v7, 10, v90
	v_lshlrev_b32_e32 v6, 10, v92
	v_lshlrev_b32_e32 v3, 10, v133
	v_lshlrev_b32_e32 v2, 10, v134
	s_cbranch_scc0 .LBB0_1452
	v_add_u32_e32 v0, s60, v96
	v_add_u32_e32 v130, v32, v0
	v_ashrrev_i32_e32 v131, 31, v130
	v_cvt_pk_bf16_f32 v63, v126, s0
	v_lshl_add_u64 v[130:131], v[130:131], 1, s[8:9]
	global_store_short v[130:131], v63, off sc1
	v_add_u32_e32 v130, v31, v0
	v_ashrrev_i32_e32 v131, 31, v130
	v_cvt_pk_bf16_f32 v63, v124, s0
	v_lshl_add_u64 v[130:131], v[130:131], 1, s[8:9]
	global_store_short v[130:131], v63, off sc1
	v_add_u32_e32 v130, v28, v0
	v_ashrrev_i32_e32 v131, 31, v130
	v_cvt_pk_bf16_f32 v63, v122, s0
	v_lshl_add_u64 v[130:131], v[130:131], 1, s[8:9]
	global_store_short v[130:131], v63, off sc1
	v_add_u32_e32 v130, v27, v0
	v_ashrrev_i32_e32 v131, 31, v130
	v_cvt_pk_bf16_f32 v63, v93, s0
	v_lshl_add_u64 v[130:131], v[130:131], 1, s[8:9]
	global_store_short v[130:131], v63, off sc1
	v_add_u32_e32 v130, v24, v0
	v_ashrrev_i32_e32 v131, 31, v130
	v_cvt_pk_bf16_f32 v63, v91, s0
	v_lshl_add_u64 v[130:131], v[130:131], 1, s[8:9]
	global_store_short v[130:131], v63, off sc1
	v_add_u32_e32 v130, v23, v0
	v_ashrrev_i32_e32 v131, 31, v130
	v_cvt_pk_bf16_f32 v63, v89, s0
	v_lshl_add_u64 v[130:131], v[130:131], 1, s[8:9]
	global_store_short v[130:131], v63, off sc1
	v_add_u32_e32 v130, v20, v0
	v_ashrrev_i32_e32 v131, 31, v130
	v_cvt_pk_bf16_f32 v63, v87, s0
	v_lshl_add_u64 v[130:131], v[130:131], 1, s[8:9]
	global_store_short v[130:131], v63, off sc1
	v_add_u32_e32 v130, v14, v0
	v_ashrrev_i32_e32 v131, 31, v130
	v_cvt_pk_bf16_f32 v63, v85, s0
	v_lshl_add_u64 v[130:131], v[130:131], 1, s[8:9]
	global_store_short v[130:131], v63, off sc1
	v_add_u32_e32 v130, v13, v0
	v_ashrrev_i32_e32 v131, 31, v130
	v_cvt_pk_bf16_f32 v63, v83, s0
	v_lshl_add_u64 v[130:131], v[130:131], 1, s[8:9]
	global_store_short v[130:131], v63, off sc1
	v_add_u32_e32 v130, v12, v0
	v_ashrrev_i32_e32 v131, 31, v130
	v_cvt_pk_bf16_f32 v63, v75, s0
	v_lshl_add_u64 v[130:131], v[130:131], 1, s[8:9]
	global_store_short v[130:131], v63, off sc1
	v_add_u32_e32 v130, v11, v0
	v_ashrrev_i32_e32 v131, 31, v130
	v_cvt_pk_bf16_f32 v63, v74, s0
	v_lshl_add_u64 v[130:131], v[130:131], 1, s[8:9]
	global_store_short v[130:131], v63, off sc1
	v_add_u32_e32 v130, v10, v0
	v_ashrrev_i32_e32 v131, 31, v130
	v_cvt_pk_bf16_f32 v63, v73, s0
	v_lshl_add_u64 v[130:131], v[130:131], 1, s[8:9]
	global_store_short v[130:131], v63, off sc1
	v_add_u32_e32 v130, v7, v0
	v_ashrrev_i32_e32 v131, 31, v130
	v_cvt_pk_bf16_f32 v63, v72, s0
	v_lshl_add_u64 v[130:131], v[130:131], 1, s[8:9]
	global_store_short v[130:131], v63, off sc1
	v_add_u32_e32 v130, v6, v0
	v_ashrrev_i32_e32 v131, 31, v130
	v_cvt_pk_bf16_f32 v63, v71, s0
	v_lshl_add_u64 v[130:131], v[130:131], 1, s[8:9]
	global_store_short v[130:131], v63, off sc1
	v_add_u32_e32 v130, v3, v0
	v_ashrrev_i32_e32 v131, 31, v130
	v_cvt_pk_bf16_f32 v63, v70, s0
	v_lshl_add_u64 v[130:131], v[130:131], 1, s[8:9]
	global_store_short v[130:131], v63, off sc1
	v_add_u32_e32 v130, v2, v0
	v_ashrrev_i32_e32 v131, 31, v130
	v_cvt_pk_bf16_f32 v63, v69, s0
	v_lshl_add_u64 v[130:131], v[130:131], 1, s[8:9]
	global_store_short v[130:131], v63, off sc1
	v_or_b32_e32 v63, 32, v0
	v_add_u32_e32 v130, v32, v63
	v_ashrrev_i32_e32 v131, 31, v130
	v_cvt_pk_bf16_f32 v68, v62, s0
	v_lshl_add_u64 v[130:131], v[130:131], 1, s[8:9]
	global_store_short v[130:131], v68, off sc1
	v_add_u32_e32 v130, v31, v63
	v_ashrrev_i32_e32 v131, 31, v130
	v_cvt_pk_bf16_f32 v68, v61, s0
	v_lshl_add_u64 v[130:131], v[130:131], 1, s[8:9]
	global_store_short v[130:131], v68, off sc1
	v_add_u32_e32 v130, v28, v63
	v_ashrrev_i32_e32 v131, 31, v130
	v_cvt_pk_bf16_f32 v68, v60, s0
	v_lshl_add_u64 v[130:131], v[130:131], 1, s[8:9]
	global_store_short v[130:131], v68, off sc1
	v_add_u32_e32 v130, v27, v63
	v_ashrrev_i32_e32 v131, 31, v130
	v_cvt_pk_bf16_f32 v68, v59, s0
	v_lshl_add_u64 v[130:131], v[130:131], 1, s[8:9]
	global_store_short v[130:131], v68, off sc1
	v_add_u32_e32 v130, v24, v63
	v_ashrrev_i32_e32 v131, 31, v130
	v_cvt_pk_bf16_f32 v68, v58, s0
	v_lshl_add_u64 v[130:131], v[130:131], 1, s[8:9]
	global_store_short v[130:131], v68, off sc1
	v_add_u32_e32 v130, v23, v63
	v_ashrrev_i32_e32 v131, 31, v130
	v_cvt_pk_bf16_f32 v68, v57, s0
	v_lshl_add_u64 v[130:131], v[130:131], 1, s[8:9]
	global_store_short v[130:131], v68, off sc1
	v_add_u32_e32 v130, v20, v63
	v_ashrrev_i32_e32 v131, 31, v130
	v_cvt_pk_bf16_f32 v68, v56, s0
	v_lshl_add_u64 v[130:131], v[130:131], 1, s[8:9]
	global_store_short v[130:131], v68, off sc1
	v_add_u32_e32 v130, v14, v63
	v_ashrrev_i32_e32 v131, 31, v130
	v_cvt_pk_bf16_f32 v68, v55, s0
	v_lshl_add_u64 v[130:131], v[130:131], 1, s[8:9]
	global_store_short v[130:131], v68, off sc1
	v_add_u32_e32 v130, v13, v63
	v_ashrrev_i32_e32 v131, 31, v130
	v_cvt_pk_bf16_f32 v68, v54, s0
	v_lshl_add_u64 v[130:131], v[130:131], 1, s[8:9]
	global_store_short v[130:131], v68, off sc1
	v_add_u32_e32 v130, v12, v63
	v_ashrrev_i32_e32 v131, 31, v130
	v_cvt_pk_bf16_f32 v68, v53, s0
	v_lshl_add_u64 v[130:131], v[130:131], 1, s[8:9]
	global_store_short v[130:131], v68, off sc1
	v_add_u32_e32 v130, v11, v63
	v_ashrrev_i32_e32 v131, 31, v130
	v_cvt_pk_bf16_f32 v68, v52, s0
	v_lshl_add_u64 v[130:131], v[130:131], 1, s[8:9]
	global_store_short v[130:131], v68, off sc1
	v_add_u32_e32 v130, v10, v63
	v_ashrrev_i32_e32 v131, 31, v130
	v_cvt_pk_bf16_f32 v68, v51, s0
	v_lshl_add_u64 v[130:131], v[130:131], 1, s[8:9]
	global_store_short v[130:131], v68, off sc1
	v_add_u32_e32 v130, v7, v63
	v_ashrrev_i32_e32 v131, 31, v130
	v_cvt_pk_bf16_f32 v68, v50, s0
	v_lshl_add_u64 v[130:131], v[130:131], 1, s[8:9]
	global_store_short v[130:131], v68, off sc1
	v_add_u32_e32 v130, v6, v63
	v_ashrrev_i32_e32 v131, 31, v130
	v_cvt_pk_bf16_f32 v68, v49, s0
	v_lshl_add_u64 v[130:131], v[130:131], 1, s[8:9]
	global_store_short v[130:131], v68, off sc1
	v_add_u32_e32 v130, v3, v63
	v_ashrrev_i32_e32 v131, 31, v130
	v_cvt_pk_bf16_f32 v68, v48, s0
	v_lshl_add_u64 v[130:131], v[130:131], 1, s[8:9]
	global_store_short v[130:131], v68, off sc1
	v_add_u32_e32 v130, v2, v63
	v_ashrrev_i32_e32 v131, 31, v130
	v_cvt_pk_bf16_f32 v68, v67, s0
	v_lshl_add_u64 v[130:131], v[130:131], 1, s[8:9]
	v_or_b32_e32 v63, 64, v0
	global_store_short v[130:131], v68, off sc1
	v_add_u32_e32 v130, v32, v63
	v_ashrrev_i32_e32 v131, 31, v130
	v_cvt_pk_bf16_f32 v68, v47, s0
	v_lshl_add_u64 v[130:131], v[130:131], 1, s[8:9]
	global_store_short v[130:131], v68, off sc1
	v_add_u32_e32 v130, v31, v63
	v_ashrrev_i32_e32 v131, 31, v130
	v_cvt_pk_bf16_f32 v68, v46, s0
	v_lshl_add_u64 v[130:131], v[130:131], 1, s[8:9]
	global_store_short v[130:131], v68, off sc1
	v_add_u32_e32 v130, v28, v63
	v_ashrrev_i32_e32 v131, 31, v130
	v_cvt_pk_bf16_f32 v68, v45, s0
	v_lshl_add_u64 v[130:131], v[130:131], 1, s[8:9]
	global_store_short v[130:131], v68, off sc1
	v_add_u32_e32 v130, v27, v63
	v_ashrrev_i32_e32 v131, 31, v130
	v_cvt_pk_bf16_f32 v68, v44, s0
	v_lshl_add_u64 v[130:131], v[130:131], 1, s[8:9]
	global_store_short v[130:131], v68, off sc1
	v_add_u32_e32 v130, v24, v63
	v_ashrrev_i32_e32 v131, 31, v130
	v_cvt_pk_bf16_f32 v68, v43, s0
	v_lshl_add_u64 v[130:131], v[130:131], 1, s[8:9]
	global_store_short v[130:131], v68, off sc1
	v_add_u32_e32 v130, v23, v63
	v_ashrrev_i32_e32 v131, 31, v130
	v_cvt_pk_bf16_f32 v68, v42, s0
	v_lshl_add_u64 v[130:131], v[130:131], 1, s[8:9]
	global_store_short v[130:131], v68, off sc1
	v_add_u32_e32 v130, v20, v63
	v_ashrrev_i32_e32 v131, 31, v130
	v_cvt_pk_bf16_f32 v68, v41, s0
	v_lshl_add_u64 v[130:131], v[130:131], 1, s[8:9]
	global_store_short v[130:131], v68, off sc1
	v_add_u32_e32 v130, v14, v63
	v_ashrrev_i32_e32 v131, 31, v130
	v_cvt_pk_bf16_f32 v68, v40, s0
	v_lshl_add_u64 v[130:131], v[130:131], 1, s[8:9]
	global_store_short v[130:131], v68, off sc1
	v_add_u32_e32 v130, v13, v63
	v_ashrrev_i32_e32 v131, 31, v130
	v_cvt_pk_bf16_f32 v68, v39, s0
	v_lshl_add_u64 v[130:131], v[130:131], 1, s[8:9]
	global_store_short v[130:131], v68, off sc1
	v_add_u32_e32 v130, v12, v63
	v_ashrrev_i32_e32 v131, 31, v130
	v_cvt_pk_bf16_f32 v68, v38, s0
	v_lshl_add_u64 v[130:131], v[130:131], 1, s[8:9]
	global_store_short v[130:131], v68, off sc1
	v_add_u32_e32 v130, v11, v63
	v_ashrrev_i32_e32 v131, 31, v130
	v_cvt_pk_bf16_f32 v68, v37, s0
	v_lshl_add_u64 v[130:131], v[130:131], 1, s[8:9]
	global_store_short v[130:131], v68, off sc1
	v_add_u32_e32 v130, v10, v63
	v_ashrrev_i32_e32 v131, 31, v130
	v_cvt_pk_bf16_f32 v68, v36, s0
	v_lshl_add_u64 v[130:131], v[130:131], 1, s[8:9]
	global_store_short v[130:131], v68, off sc1
	v_add_u32_e32 v130, v7, v63
	v_ashrrev_i32_e32 v131, 31, v130
	v_cvt_pk_bf16_f32 v68, v35, s0
	v_lshl_add_u64 v[130:131], v[130:131], 1, s[8:9]
	global_store_short v[130:131], v68, off sc1
	v_add_u32_e32 v130, v6, v63
	v_ashrrev_i32_e32 v131, 31, v130
	v_cvt_pk_bf16_f32 v68, v34, s0
	v_lshl_add_u64 v[130:131], v[130:131], 1, s[8:9]
	global_store_short v[130:131], v68, off sc1
	v_add_u32_e32 v130, v3, v63
	v_ashrrev_i32_e32 v131, 31, v130
	v_cvt_pk_bf16_f32 v68, v33, s0
	v_lshl_add_u64 v[130:131], v[130:131], 1, s[8:9]
	global_store_short v[130:131], v68, off sc1
	v_add_u32_e32 v130, v2, v63
	v_ashrrev_i32_e32 v131, 31, v130
	v_cvt_pk_bf16_f32 v68, v66, s0
	v_lshl_add_u64 v[130:131], v[130:131], 1, s[8:9]
	v_or_b32_e32 v0, 0x60, v0
	global_store_short v[130:131], v68, off sc1
	v_add_u32_e32 v130, v32, v0
	v_ashrrev_i32_e32 v131, 31, v130
	v_cvt_pk_bf16_f32 v63, v30, s0
	v_lshl_add_u64 v[130:131], v[130:131], 1, s[8:9]
	global_store_short v[130:131], v63, off sc1
	v_add_u32_e32 v130, v31, v0
	v_ashrrev_i32_e32 v131, 31, v130
	v_cvt_pk_bf16_f32 v63, v29, s0
	v_lshl_add_u64 v[130:131], v[130:131], 1, s[8:9]
	global_store_short v[130:131], v63, off sc1
	v_add_u32_e32 v130, v28, v0
	v_ashrrev_i32_e32 v131, 31, v130
	v_cvt_pk_bf16_f32 v63, v26, s0
	v_lshl_add_u64 v[130:131], v[130:131], 1, s[8:9]
	global_store_short v[130:131], v63, off sc1
	v_add_u32_e32 v130, v27, v0
	v_ashrrev_i32_e32 v131, 31, v130
	v_cvt_pk_bf16_f32 v63, v25, s0
	v_lshl_add_u64 v[130:131], v[130:131], 1, s[8:9]
	global_store_short v[130:131], v63, off sc1
	v_add_u32_e32 v130, v24, v0
	v_ashrrev_i32_e32 v131, 31, v130
	v_cvt_pk_bf16_f32 v63, v22, s0
	v_lshl_add_u64 v[130:131], v[130:131], 1, s[8:9]
	global_store_short v[130:131], v63, off sc1
	v_add_u32_e32 v130, v23, v0
	v_ashrrev_i32_e32 v131, 31, v130
	v_cvt_pk_bf16_f32 v63, v21, s0
	v_lshl_add_u64 v[130:131], v[130:131], 1, s[8:9]
	global_store_short v[130:131], v63, off sc1
	v_add_u32_e32 v130, v20, v0
	v_ashrrev_i32_e32 v131, 31, v130
	v_cvt_pk_bf16_f32 v63, v19, s0
	v_lshl_add_u64 v[130:131], v[130:131], 1, s[8:9]
	global_store_short v[130:131], v63, off sc1
	v_add_u32_e32 v130, v14, v0
	v_ashrrev_i32_e32 v131, 31, v130
	v_cvt_pk_bf16_f32 v63, v18, s0
	v_lshl_add_u64 v[130:131], v[130:131], 1, s[8:9]
	global_store_short v[130:131], v63, off sc1
	v_add_u32_e32 v130, v13, v0
	v_ashrrev_i32_e32 v131, 31, v130
	v_cvt_pk_bf16_f32 v63, v17, s0
	v_lshl_add_u64 v[130:131], v[130:131], 1, s[8:9]
	global_store_short v[130:131], v63, off sc1
	v_add_u32_e32 v130, v12, v0
	v_ashrrev_i32_e32 v131, 31, v130
	v_cvt_pk_bf16_f32 v63, v16, s0
	v_lshl_add_u64 v[130:131], v[130:131], 1, s[8:9]
	global_store_short v[130:131], v63, off sc1
	v_add_u32_e32 v130, v11, v0
	v_ashrrev_i32_e32 v131, 31, v130
	v_cvt_pk_bf16_f32 v63, v9, s0
	v_lshl_add_u64 v[130:131], v[130:131], 1, s[8:9]
	global_store_short v[130:131], v63, off sc1
	v_add_u32_e32 v130, v10, v0
	v_ashrrev_i32_e32 v131, 31, v130
	v_cvt_pk_bf16_f32 v63, v8, s0
	v_lshl_add_u64 v[130:131], v[130:131], 1, s[8:9]
	global_store_short v[130:131], v63, off sc1
	v_add_u32_e32 v130, v7, v0
	v_ashrrev_i32_e32 v131, 31, v130
	v_cvt_pk_bf16_f32 v63, v5, s0
	v_lshl_add_u64 v[130:131], v[130:131], 1, s[8:9]
	global_store_short v[130:131], v63, off sc1
	v_add_u32_e32 v130, v6, v0
	v_ashrrev_i32_e32 v131, 31, v130
	v_cvt_pk_bf16_f32 v63, v4, s0
	v_lshl_add_u64 v[130:131], v[130:131], 1, s[8:9]
	global_store_short v[130:131], v63, off sc1
	v_add_u32_e32 v130, v3, v0
	v_ashrrev_i32_e32 v131, 31, v130
	v_cvt_pk_bf16_f32 v63, v1, s0
	v_lshl_add_u64 v[130:131], v[130:131], 1, s[8:9]
	global_store_short v[130:131], v63, off sc1
	v_add_u32_e32 v0, v2, v0
	s_mov_b64 s[62:63], 0
.LBB0_1452:
	v_fmac_f32_e32 v65, v15, v128
	s_andn2_b64 vcc, exec, s[62:63]
	s_mov_b64 s[60:61], 0x13f9f000
	s_cbranch_vccnz .LBB0_1445
	v_mul_f32_e32 v0, 0x3d372713, v126
	v_mul_f32_e32 v0, v126, v0
	v_fma_f32 v0, v126, v0, v126
	v_mul_f32_e32 v0, 0xbfcc422a, v0
	v_mul_f32_e32 v82, 0x3d372713, v124
	v_mul_f32_e32 v0, 0x3fb8aa3b, v0
	v_mul_f32_e32 v82, v124, v82
	v_exp_f32_e32 v68, v0
	v_fma_f32 v82, v124, v82, v124
	v_mul_f32_e32 v82, 0xbfcc422a, v82
	v_mul_f32_e32 v82, 0x3fb8aa3b, v82
	v_exp_f32_e32 v82, v82
	v_add_f32_e32 v68, 1.0, v68
	v_rcp_f32_e32 v68, v68
	v_add_u32_e32 v92, v27, v64
	v_add_f32_e32 v82, 1.0, v82
	v_rcp_f32_e32 v82, v82
	v_mul_f32_e32 v68, v126, v68
	v_add_u32_e32 v126, v32, v64
	v_ashrrev_i32_e32 v127, 31, v126
	v_cvt_pk_bf16_f32 v68, v68, s0
	v_lshl_add_u64 v[126:127], v[126:127], 1, s[18:19]
	global_store_short v[126:127], v68, off sc1
	v_mul_f32_e32 v68, v124, v82
	v_mul_f32_e32 v82, 0x3d372713, v122
	v_mul_f32_e32 v82, v122, v82
	v_fma_f32 v82, v122, v82, v122
	v_mul_f32_e32 v82, 0xbfcc422a, v82
	v_mul_f32_e32 v82, 0x3fb8aa3b, v82
	v_exp_f32_e32 v82, v82
	v_add_u32_e32 v124, v31, v64
	v_ashrrev_i32_e32 v125, 31, v124
	v_cvt_pk_bf16_f32 v68, v68, s0
	v_lshl_add_u64 v[124:125], v[124:125], 1, s[18:19]
	global_store_short v[124:125], v68, off sc1
	v_add_f32_e32 v68, 1.0, v82
	v_mul_f32_e32 v82, 0x3d372713, v93
	v_mul_f32_e32 v82, v93, v82
	v_fma_f32 v82, v93, v82, v93
	v_mul_f32_e32 v82, 0xbfcc422a, v82
	v_mul_f32_e32 v82, 0x3fb8aa3b, v82
	v_exp_f32_e32 v82, v82
	v_rcp_f32_e32 v68, v68
	v_add_u32_e32 v90, v24, v64
	v_add_u32_e32 v88, v23, v64
	v_add_f32_e32 v82, 1.0, v82
	v_rcp_f32_e32 v82, v82
	v_mul_f32_e32 v68, v122, v68
	v_add_u32_e32 v122, v28, v64
	v_ashrrev_i32_e32 v123, 31, v122
	v_cvt_pk_bf16_f32 v68, v68, s0
	v_lshl_add_u64 v[122:123], v[122:123], 1, s[18:19]
	global_store_short v[122:123], v68, off sc1
	v_mul_f32_e32 v68, v93, v82
	v_mul_f32_e32 v82, 0x3d372713, v91
	v_mul_f32_e32 v82, v91, v82
	v_fma_f32 v82, v91, v82, v91
	v_mul_f32_e32 v82, 0xbfcc422a, v82
	v_mul_f32_e32 v82, 0x3fb8aa3b, v82
	v_exp_f32_e32 v82, v82
	v_ashrrev_i32_e32 v93, 31, v92
	v_cvt_pk_bf16_f32 v68, v68, s0
	v_lshl_add_u64 v[92:93], v[92:93], 1, s[18:19]
	global_store_short v[92:93], v68, off sc1
	v_add_f32_e32 v68, 1.0, v82
	v_mul_f32_e32 v82, 0x3d372713, v89
	v_mul_f32_e32 v82, v89, v82
	v_fma_f32 v82, v89, v82, v89
	v_mul_f32_e32 v82, 0xbfcc422a, v82
	v_mul_f32_e32 v82, 0x3fb8aa3b, v82
	v_exp_f32_e32 v82, v82
	v_rcp_f32_e32 v68, v68
	v_add_u32_e32 v86, v20, v64
	v_add_u32_e32 v84, v14, v64
	v_add_f32_e32 v82, 1.0, v82
	v_rcp_f32_e32 v82, v82
	v_mul_f32_e32 v68, v91, v68
	v_ashrrev_i32_e32 v91, 31, v90
	v_cvt_pk_bf16_f32 v68, v68, s0
	v_lshl_add_u64 v[90:91], v[90:91], 1, s[18:19]
	global_store_short v[90:91], v68, off sc1
	v_mul_f32_e32 v68, v89, v82
	v_mul_f32_e32 v82, 0x3d372713, v87
	v_mul_f32_e32 v82, v87, v82
	v_fma_f32 v82, v87, v82, v87
	v_mul_f32_e32 v82, 0xbfcc422a, v82
	v_mul_f32_e32 v82, 0x3fb8aa3b, v82
	v_exp_f32_e32 v82, v82
	v_ashrrev_i32_e32 v89, 31, v88
	v_cvt_pk_bf16_f32 v68, v68, s0
	v_lshl_add_u64 v[88:89], v[88:89], 1, s[18:19]
	global_store_short v[88:89], v68, off sc1
	v_add_f32_e32 v68, 1.0, v82
	v_mul_f32_e32 v82, 0x3d372713, v85
	v_mul_f32_e32 v82, v85, v82
	v_fma_f32 v82, v85, v82, v85
	v_mul_f32_e32 v82, 0xbfcc422a, v82
	v_mul_f32_e32 v82, 0x3fb8aa3b, v82
	v_exp_f32_e32 v82, v82
	v_rcp_f32_e32 v68, v68
	v_or_b32_e32 v63, 32, v64
	v_or_b32_e32 v15, 64, v64
	v_add_f32_e32 v82, 1.0, v82
	v_rcp_f32_e32 v82, v82
	v_mul_f32_e32 v68, v87, v68
	v_ashrrev_i32_e32 v87, 31, v86
	v_cvt_pk_bf16_f32 v68, v68, s0
	v_lshl_add_u64 v[86:87], v[86:87], 1, s[18:19]
	global_store_short v[86:87], v68, off sc1
	v_mul_f32_e32 v68, v85, v82
	v_mul_f32_e32 v82, 0x3d372713, v83
	v_mul_f32_e32 v82, v83, v82
	v_fma_f32 v82, v83, v82, v83
	v_mul_f32_e32 v82, 0xbfcc422a, v82
	v_mul_f32_e32 v82, 0x3fb8aa3b, v82
	v_exp_f32_e32 v82, v82
	v_ashrrev_i32_e32 v85, 31, v84
	v_cvt_pk_bf16_f32 v68, v68, s0
	v_lshl_add_u64 v[84:85], v[84:85], 1, s[18:19]
	global_store_short v[84:85], v68, off sc1
	v_add_f32_e32 v68, 1.0, v82
	v_mul_f32_e32 v82, 0x3d372713, v75
	v_mul_f32_e32 v82, v75, v82
	v_fma_f32 v82, v75, v82, v75
	v_mul_f32_e32 v82, 0xbfcc422a, v82
	v_mul_f32_e32 v82, 0x3fb8aa3b, v82
	v_rcp_f32_e32 v68, v68
	v_exp_f32_e32 v84, v82
	v_add_u32_e32 v82, v13, v64
	v_or_b32_e32 v0, 0x60, v64
	v_mul_f32_e32 v68, v83, v68
	v_add_f32_e32 v83, 1.0, v84
	v_rcp_f32_e32 v84, v83
	v_ashrrev_i32_e32 v83, 31, v82
	v_cvt_pk_bf16_f32 v68, v68, s0
	v_lshl_add_u64 v[82:83], v[82:83], 1, s[18:19]
	global_store_short v[82:83], v68, off sc1
	v_mul_f32_e32 v68, v75, v84
	v_mul_f32_e32 v75, 0x3d372713, v74
	v_mul_f32_e32 v75, v74, v75
	v_fma_f32 v75, v74, v75, v74
	v_mul_f32_e32 v75, 0xbfcc422a, v75
	v_mul_f32_e32 v75, 0x3fb8aa3b, v75
	v_exp_f32_e32 v75, v75
	v_add_u32_e32 v82, v12, v64
	v_ashrrev_i32_e32 v83, 31, v82
	v_cvt_pk_bf16_f32 v68, v68, s0
	v_lshl_add_u64 v[82:83], v[82:83], 1, s[18:19]
	global_store_short v[82:83], v68, off sc1
	v_add_f32_e32 v68, 1.0, v75
	v_mul_f32_e32 v75, 0x3d372713, v73
	v_mul_f32_e32 v75, v73, v75
	v_fma_f32 v75, v73, v75, v73
	v_mul_f32_e32 v75, 0xbfcc422a, v75
	v_mul_f32_e32 v75, 0x3fb8aa3b, v75
	v_exp_f32_e32 v75, v75
	v_rcp_f32_e32 v68, v68
	s_mov_b64 s[60:61], 0xdf9f000
	v_add_f32_e32 v75, 1.0, v75
	v_rcp_f32_e32 v82, v75
	v_mul_f32_e32 v68, v74, v68
	v_add_u32_e32 v74, v11, v64
	v_ashrrev_i32_e32 v75, 31, v74
	v_cvt_pk_bf16_f32 v68, v68, s0
	v_lshl_add_u64 v[74:75], v[74:75], 1, s[18:19]
	global_store_short v[74:75], v68, off sc1
	v_mul_f32_e32 v68, v73, v82
	v_mul_f32_e32 v73, 0x3d372713, v72
	v_mul_f32_e32 v73, v72, v73
	v_fma_f32 v73, v72, v73, v72
	v_mul_f32_e32 v73, 0xbfcc422a, v73
	v_mul_f32_e32 v73, 0x3fb8aa3b, v73
	v_exp_f32_e32 v73, v73
	v_add_u32_e32 v74, v10, v64
	v_ashrrev_i32_e32 v75, 31, v74
	v_cvt_pk_bf16_f32 v68, v68, s0
	v_lshl_add_u64 v[74:75], v[74:75], 1, s[18:19]
	global_store_short v[74:75], v68, off sc1
	v_add_f32_e32 v68, 1.0, v73
	v_mul_f32_e32 v73, 0x3d372713, v71
	v_mul_f32_e32 v73, v71, v73
	v_fma_f32 v73, v71, v73, v71
	v_mul_f32_e32 v73, 0xbfcc422a, v73
	v_mul_f32_e32 v73, 0x3fb8aa3b, v73
	v_exp_f32_e32 v73, v73
	v_rcp_f32_e32 v68, v68
	v_add_f32_e32 v73, 1.0, v73
	v_rcp_f32_e32 v74, v73
	v_mul_f32_e32 v68, v72, v68
	v_add_u32_e32 v72, v7, v64
	v_ashrrev_i32_e32 v73, 31, v72
	v_cvt_pk_bf16_f32 v68, v68, s0
	v_lshl_add_u64 v[72:73], v[72:73], 1, s[18:19]
	global_store_short v[72:73], v68, off sc1
	v_mul_f32_e32 v68, v71, v74
	v_mul_f32_e32 v71, 0x3d372713, v70
	v_mul_f32_e32 v71, v70, v71
	v_fma_f32 v71, v70, v71, v70
	v_mul_f32_e32 v71, 0xbfcc422a, v71
	v_mul_f32_e32 v71, 0x3fb8aa3b, v71
	v_exp_f32_e32 v71, v71
	v_add_u32_e32 v72, v6, v64
	v_ashrrev_i32_e32 v73, 31, v72
	v_cvt_pk_bf16_f32 v68, v68, s0
	v_lshl_add_u64 v[72:73], v[72:73], 1, s[18:19]
	global_store_short v[72:73], v68, off sc1
	v_add_f32_e32 v68, 1.0, v71
	v_mul_f32_e32 v71, 0x3d372713, v69
	v_mul_f32_e32 v71, v69, v71
	v_fma_f32 v71, v69, v71, v69
	v_mul_f32_e32 v71, 0xbfcc422a, v71
	v_mul_f32_e32 v71, 0x3fb8aa3b, v71
	v_exp_f32_e32 v71, v71
	v_rcp_f32_e32 v68, v68
	v_add_f32_e32 v71, 1.0, v71
	v_rcp_f32_e32 v72, v71
	v_mul_f32_e32 v68, v70, v68
	v_add_u32_e32 v70, v3, v64
	v_ashrrev_i32_e32 v71, 31, v70
	v_cvt_pk_bf16_f32 v68, v68, s0
	v_lshl_add_u64 v[70:71], v[70:71], 1, s[18:19]
	global_store_short v[70:71], v68, off sc1
	v_mul_f32_e32 v68, v69, v72
	v_cvt_pk_bf16_f32 v70, v68, s0
	v_add_u32_e32 v68, v2, v64
	v_mul_f32_e32 v64, 0x3d372713, v62
	v_mul_f32_e32 v64, v62, v64
	v_fma_f32 v64, v62, v64, v62
	v_mul_f32_e32 v64, 0xbfcc422a, v64
	v_ashrrev_i32_e32 v69, 31, v68
	v_mul_f32_e32 v64, 0x3fb8aa3b, v64
	v_lshl_add_u64 v[68:69], v[68:69], 1, s[18:19]
	v_exp_f32_e32 v64, v64
	global_store_short v[68:69], v70, off sc1
	v_mul_f32_e32 v68, 0x3d372713, v61
	v_mul_f32_e32 v68, v61, v68
	v_fma_f32 v68, v61, v68, v61
	v_mul_f32_e32 v68, 0xbfcc422a, v68
	v_add_f32_e32 v64, 1.0, v64
	v_mul_f32_e32 v68, 0x3fb8aa3b, v68
	v_rcp_f32_e32 v64, v64
	v_exp_f32_e32 v69, v68
	v_add_u32_e32 v68, v32, v63
	v_mul_f32_e32 v62, v62, v64
	v_add_f32_e32 v64, 1.0, v69
	v_ashrrev_i32_e32 v69, 31, v68
	v_cvt_pk_bf16_f32 v62, v62, s0
	v_lshl_add_u64 v[68:69], v[68:69], 1, s[18:19]
	global_store_short v[68:69], v62, off sc1
	v_mul_f32_e32 v62, 0x3d372713, v60
	v_mul_f32_e32 v62, v60, v62
	v_fma_f32 v62, v60, v62, v60
	v_rcp_f32_e32 v64, v64
	v_mul_f32_e32 v62, 0xbfcc422a, v62
	v_mul_f32_e32 v62, 0x3fb8aa3b, v62
	v_exp_f32_e32 v62, v62
	v_add_u32_e32 v68, v31, v63
	v_mul_f32_e32 v61, v61, v64
	v_ashrrev_i32_e32 v69, 31, v68
	v_cvt_pk_bf16_f32 v61, v61, s0
	v_lshl_add_u64 v[68:69], v[68:69], 1, s[18:19]
	global_store_short v[68:69], v61, off sc1
	v_add_f32_e32 v61, 1.0, v62
	v_mul_f32_e32 v62, 0x3d372713, v59
	v_mul_f32_e32 v62, v59, v62
	v_fma_f32 v62, v59, v62, v59
	v_mul_f32_e32 v62, 0xbfcc422a, v62
	v_rcp_f32_e32 v61, v61
	v_mul_f32_e32 v62, 0x3fb8aa3b, v62
	v_exp_f32_e32 v62, v62
	v_mul_f32_e32 v60, v60, v61
	v_cvt_pk_bf16_f32 v64, v60, s0
	v_add_u32_e32 v60, v28, v63
	v_add_f32_e32 v61, 1.0, v62
	v_rcp_f32_e32 v62, v61
	v_ashrrev_i32_e32 v61, 31, v60
	v_lshl_add_u64 v[60:61], v[60:61], 1, s[18:19]
	global_store_short v[60:61], v64, off sc1
	v_mul_f32_e32 v61, 0x3d372713, v58
	v_mul_f32_e32 v61, v58, v61
	v_fma_f32 v61, v58, v61, v58
	v_mul_f32_e32 v61, 0xbfcc422a, v61
	v_add_u32_e32 v60, v27, v63
	v_mul_f32_e32 v61, 0x3fb8aa3b, v61
	v_mul_f32_e32 v59, v59, v62
	v_exp_f32_e32 v62, v61
	v_ashrrev_i32_e32 v61, 31, v60
	v_cvt_pk_bf16_f32 v59, v59, s0
	v_lshl_add_u64 v[60:61], v[60:61], 1, s[18:19]
	global_store_short v[60:61], v59, off sc1
	v_mul_f32_e32 v60, 0x3d372713, v57
	v_mul_f32_e32 v60, v57, v60
	v_fma_f32 v60, v57, v60, v57
	v_add_f32_e32 v59, 1.0, v62
	v_mul_f32_e32 v60, 0xbfcc422a, v60
	v_rcp_f32_e32 v59, v59
	v_mul_f32_e32 v60, 0x3fb8aa3b, v60
	v_exp_f32_e32 v60, v60
	v_mul_f32_e32 v58, v58, v59
	v_cvt_pk_bf16_f32 v61, v58, s0
	v_add_u32_e32 v58, v24, v63
	v_add_f32_e32 v59, 1.0, v60
	v_rcp_f32_e32 v60, v59
	v_ashrrev_i32_e32 v59, 31, v58
	v_lshl_add_u64 v[58:59], v[58:59], 1, s[18:19]
	global_store_short v[58:59], v61, off sc1
	v_mul_f32_e32 v59, 0x3d372713, v56
	v_mul_f32_e32 v59, v56, v59
	v_fma_f32 v59, v56, v59, v56
	v_mul_f32_e32 v59, 0xbfcc422a, v59
	v_add_u32_e32 v58, v23, v63
	v_mul_f32_e32 v59, 0x3fb8aa3b, v59
	v_mul_f32_e32 v57, v57, v60
	v_exp_f32_e32 v60, v59
	v_ashrrev_i32_e32 v59, 31, v58
	v_cvt_pk_bf16_f32 v57, v57, s0
	v_lshl_add_u64 v[58:59], v[58:59], 1, s[18:19]
	global_store_short v[58:59], v57, off sc1
	v_mul_f32_e32 v58, 0x3d372713, v55
	v_mul_f32_e32 v58, v55, v58
	v_fma_f32 v58, v55, v58, v55
	v_add_f32_e32 v57, 1.0, v60
	v_mul_f32_e32 v58, 0xbfcc422a, v58
	v_rcp_f32_e32 v57, v57
	v_mul_f32_e32 v58, 0x3fb8aa3b, v58
	v_exp_f32_e32 v58, v58
	v_mul_f32_e32 v56, v56, v57
	v_cvt_pk_bf16_f32 v59, v56, s0
	v_add_u32_e32 v56, v20, v63
	v_add_f32_e32 v57, 1.0, v58
	v_rcp_f32_e32 v58, v57
	v_ashrrev_i32_e32 v57, 31, v56
	v_lshl_add_u64 v[56:57], v[56:57], 1, s[18:19]
	global_store_short v[56:57], v59, off sc1
	v_mul_f32_e32 v57, 0x3d372713, v54
	v_mul_f32_e32 v57, v54, v57
	v_fma_f32 v57, v54, v57, v54
	v_mul_f32_e32 v57, 0xbfcc422a, v57
	v_add_u32_e32 v56, v14, v63
	v_mul_f32_e32 v57, 0x3fb8aa3b, v57
	v_mul_f32_e32 v55, v55, v58
	v_exp_f32_e32 v58, v57
	v_ashrrev_i32_e32 v57, 31, v56
	v_cvt_pk_bf16_f32 v55, v55, s0
	v_lshl_add_u64 v[56:57], v[56:57], 1, s[18:19]
	global_store_short v[56:57], v55, off sc1
	v_mul_f32_e32 v56, 0x3d372713, v53
	v_mul_f32_e32 v56, v53, v56
	v_fma_f32 v56, v53, v56, v53
	v_add_f32_e32 v55, 1.0, v58
	v_mul_f32_e32 v56, 0xbfcc422a, v56
	v_rcp_f32_e32 v55, v55
	v_mul_f32_e32 v56, 0x3fb8aa3b, v56
	v_exp_f32_e32 v56, v56
	v_mul_f32_e32 v54, v54, v55
	v_cvt_pk_bf16_f32 v57, v54, s0
	v_add_u32_e32 v54, v13, v63
	v_add_f32_e32 v55, 1.0, v56
	v_rcp_f32_e32 v56, v55
	v_ashrrev_i32_e32 v55, 31, v54
	v_lshl_add_u64 v[54:55], v[54:55], 1, s[18:19]
	global_store_short v[54:55], v57, off sc1
	v_mul_f32_e32 v55, 0x3d372713, v52
	v_mul_f32_e32 v55, v52, v55
	v_fma_f32 v55, v52, v55, v52
	v_mul_f32_e32 v55, 0xbfcc422a, v55
	v_add_u32_e32 v54, v12, v63
	v_mul_f32_e32 v55, 0x3fb8aa3b, v55
	v_mul_f32_e32 v53, v53, v56
	v_exp_f32_e32 v56, v55
	v_ashrrev_i32_e32 v55, 31, v54
	v_cvt_pk_bf16_f32 v53, v53, s0
	v_lshl_add_u64 v[54:55], v[54:55], 1, s[18:19]
	global_store_short v[54:55], v53, off sc1
	v_mul_f32_e32 v54, 0x3d372713, v51
	v_mul_f32_e32 v54, v51, v54
	v_fma_f32 v54, v51, v54, v51
	v_add_f32_e32 v53, 1.0, v56
	v_mul_f32_e32 v54, 0xbfcc422a, v54
	v_rcp_f32_e32 v53, v53
	v_mul_f32_e32 v54, 0x3fb8aa3b, v54
	v_exp_f32_e32 v54, v54
	v_mul_f32_e32 v52, v52, v53
	v_cvt_pk_bf16_f32 v55, v52, s0
	v_add_u32_e32 v52, v11, v63
	v_add_f32_e32 v53, 1.0, v54
	v_rcp_f32_e32 v54, v53
	v_ashrrev_i32_e32 v53, 31, v52
	v_lshl_add_u64 v[52:53], v[52:53], 1, s[18:19]
	global_store_short v[52:53], v55, off sc1
	v_mul_f32_e32 v53, 0x3d372713, v50
	v_mul_f32_e32 v53, v50, v53
	v_fma_f32 v53, v50, v53, v50
	v_mul_f32_e32 v53, 0xbfcc422a, v53
	v_add_u32_e32 v52, v10, v63
	v_mul_f32_e32 v53, 0x3fb8aa3b, v53
	v_mul_f32_e32 v51, v51, v54
	v_exp_f32_e32 v54, v53
	v_ashrrev_i32_e32 v53, 31, v52
	v_cvt_pk_bf16_f32 v51, v51, s0
	v_lshl_add_u64 v[52:53], v[52:53], 1, s[18:19]
	global_store_short v[52:53], v51, off sc1
	v_mul_f32_e32 v52, 0x3d372713, v49
	v_mul_f32_e32 v52, v49, v52
	v_fma_f32 v52, v49, v52, v49
	v_add_f32_e32 v51, 1.0, v54
	v_mul_f32_e32 v52, 0xbfcc422a, v52
	v_rcp_f32_e32 v51, v51
	v_mul_f32_e32 v52, 0x3fb8aa3b, v52
	v_exp_f32_e32 v52, v52
	v_mul_f32_e32 v50, v50, v51
	v_cvt_pk_bf16_f32 v53, v50, s0
	v_add_u32_e32 v50, v7, v63
	v_add_f32_e32 v51, 1.0, v52
	v_rcp_f32_e32 v52, v51
	v_ashrrev_i32_e32 v51, 31, v50
	v_lshl_add_u64 v[50:51], v[50:51], 1, s[18:19]
	global_store_short v[50:51], v53, off sc1
	v_mul_f32_e32 v51, 0x3d372713, v48
	v_mul_f32_e32 v51, v48, v51
	v_fma_f32 v51, v48, v51, v48
	v_mul_f32_e32 v51, 0xbfcc422a, v51
	v_add_u32_e32 v50, v6, v63
	v_mul_f32_e32 v51, 0x3fb8aa3b, v51
	v_mul_f32_e32 v49, v49, v52
	v_exp_f32_e32 v52, v51
	v_ashrrev_i32_e32 v51, 31, v50
	v_cvt_pk_bf16_f32 v49, v49, s0
	v_lshl_add_u64 v[50:51], v[50:51], 1, s[18:19]
	global_store_short v[50:51], v49, off sc1
	v_mul_f32_e32 v50, 0x3d372713, v67
	v_mul_f32_e32 v50, v67, v50
	v_fma_f32 v50, v67, v50, v67
	v_add_f32_e32 v49, 1.0, v52
	v_mul_f32_e32 v50, 0xbfcc422a, v50
	v_rcp_f32_e32 v49, v49
	v_mul_f32_e32 v50, 0x3fb8aa3b, v50
	v_exp_f32_e32 v50, v50
	v_mul_f32_e32 v48, v48, v49
	v_cvt_pk_bf16_f32 v51, v48, s0
	v_add_u32_e32 v48, v3, v63
	v_add_f32_e32 v49, 1.0, v50
	v_rcp_f32_e32 v50, v49
	v_ashrrev_i32_e32 v49, 31, v48
	v_lshl_add_u64 v[48:49], v[48:49], 1, s[18:19]
	global_store_short v[48:49], v51, off sc1
	v_mul_f32_e32 v49, 0x3d372713, v47
	v_mul_f32_e32 v49, v47, v49
	v_fma_f32 v49, v47, v49, v47
	v_mul_f32_e32 v48, v67, v50
	v_mul_f32_e32 v49, 0xbfcc422a, v49
	v_cvt_pk_bf16_f32 v50, v48, s0
	v_add_u32_e32 v48, v2, v63
	v_mul_f32_e32 v49, 0x3fb8aa3b, v49
	v_exp_f32_e32 v51, v49
	v_ashrrev_i32_e32 v49, 31, v48
	v_lshl_add_u64 v[48:49], v[48:49], 1, s[18:19]
	global_store_short v[48:49], v50, off sc1
	v_mul_f32_e32 v49, 0x3d372713, v46
	v_mul_f32_e32 v49, v46, v49
	v_fma_f32 v49, v46, v49, v46
	v_mul_f32_e32 v49, 0xbfcc422a, v49
	v_add_f32_e32 v48, 1.0, v51
	v_mul_f32_e32 v49, 0x3fb8aa3b, v49
	v_rcp_f32_e32 v48, v48
	v_exp_f32_e32 v49, v49
	v_mul_f32_e32 v47, v47, v48
	v_add_u32_e32 v48, v32, v15
	v_add_f32_e32 v49, 1.0, v49
	v_rcp_f32_e32 v50, v49
	v_ashrrev_i32_e32 v49, 31, v48
	v_cvt_pk_bf16_f32 v47, v47, s0
	v_lshl_add_u64 v[48:49], v[48:49], 1, s[18:19]
	global_store_short v[48:49], v47, off sc1
	v_mul_f32_e32 v47, 0x3d372713, v45
	v_mul_f32_e32 v47, v45, v47
	v_fma_f32 v47, v45, v47, v45
	v_mul_f32_e32 v46, v46, v50
	v_mul_f32_e32 v47, 0xbfcc422a, v47
	v_cvt_pk_bf16_f32 v48, v46, s0
	v_add_u32_e32 v46, v31, v15
	v_mul_f32_e32 v47, 0x3fb8aa3b, v47
	v_exp_f32_e32 v49, v47
	v_ashrrev_i32_e32 v47, 31, v46
	v_lshl_add_u64 v[46:47], v[46:47], 1, s[18:19]
	global_store_short v[46:47], v48, off sc1
	v_mul_f32_e32 v47, 0x3d372713, v44
	v_mul_f32_e32 v47, v44, v47
	v_fma_f32 v47, v44, v47, v44
	v_mul_f32_e32 v47, 0xbfcc422a, v47
	v_add_f32_e32 v46, 1.0, v49
	v_mul_f32_e32 v47, 0x3fb8aa3b, v47
	v_rcp_f32_e32 v46, v46
	v_exp_f32_e32 v47, v47
	v_add_u32_e32 v32, v32, v0
	v_mul_f32_e32 v45, v45, v46
	v_add_u32_e32 v46, v28, v15
	v_add_f32_e32 v47, 1.0, v47
	v_rcp_f32_e32 v48, v47
	v_ashrrev_i32_e32 v47, 31, v46
	v_cvt_pk_bf16_f32 v45, v45, s0
	v_lshl_add_u64 v[46:47], v[46:47], 1, s[18:19]
	global_store_short v[46:47], v45, off sc1
	v_mul_f32_e32 v45, 0x3d372713, v43
	v_mul_f32_e32 v45, v43, v45
	v_fma_f32 v45, v43, v45, v43
	v_mul_f32_e32 v44, v44, v48
	v_mul_f32_e32 v45, 0xbfcc422a, v45
	v_cvt_pk_bf16_f32 v46, v44, s0
	v_add_u32_e32 v44, v27, v15
	v_mul_f32_e32 v45, 0x3fb8aa3b, v45
	v_exp_f32_e32 v47, v45
	v_ashrrev_i32_e32 v45, 31, v44
	v_lshl_add_u64 v[44:45], v[44:45], 1, s[18:19]
	global_store_short v[44:45], v46, off sc1
	v_mul_f32_e32 v45, 0x3d372713, v42
	v_mul_f32_e32 v45, v42, v45
	v_fma_f32 v45, v42, v45, v42
	v_mul_f32_e32 v45, 0xbfcc422a, v45
	v_add_f32_e32 v44, 1.0, v47
	v_mul_f32_e32 v45, 0x3fb8aa3b, v45
	v_rcp_f32_e32 v44, v44
	v_exp_f32_e32 v45, v45
	v_add_u32_e32 v28, v28, v0
	v_mul_f32_e32 v43, v43, v44
	v_add_u32_e32 v44, v24, v15
	v_add_f32_e32 v45, 1.0, v45
	v_rcp_f32_e32 v46, v45
	v_ashrrev_i32_e32 v45, 31, v44
	v_cvt_pk_bf16_f32 v43, v43, s0
	v_lshl_add_u64 v[44:45], v[44:45], 1, s[18:19]
	global_store_short v[44:45], v43, off sc1
	v_mul_f32_e32 v43, 0x3d372713, v41
	v_mul_f32_e32 v43, v41, v43
	v_fma_f32 v43, v41, v43, v41
	v_mul_f32_e32 v42, v42, v46
	v_mul_f32_e32 v43, 0xbfcc422a, v43
	v_cvt_pk_bf16_f32 v44, v42, s0
	v_add_u32_e32 v42, v23, v15
	v_mul_f32_e32 v43, 0x3fb8aa3b, v43
	v_exp_f32_e32 v45, v43
	v_ashrrev_i32_e32 v43, 31, v42
	v_lshl_add_u64 v[42:43], v[42:43], 1, s[18:19]
	global_store_short v[42:43], v44, off sc1
	v_mul_f32_e32 v43, 0x3d372713, v40
	v_mul_f32_e32 v43, v40, v43
	v_fma_f32 v43, v40, v43, v40
	v_mul_f32_e32 v43, 0xbfcc422a, v43
	v_add_f32_e32 v42, 1.0, v45
	v_mul_f32_e32 v43, 0x3fb8aa3b, v43
	v_rcp_f32_e32 v42, v42
	v_exp_f32_e32 v43, v43
	v_add_u32_e32 v24, v24, v0
	v_mul_f32_e32 v41, v41, v42
	v_add_u32_e32 v42, v20, v15
	v_add_f32_e32 v43, 1.0, v43
	v_rcp_f32_e32 v44, v43
	v_ashrrev_i32_e32 v43, 31, v42
	v_cvt_pk_bf16_f32 v41, v41, s0
	v_lshl_add_u64 v[42:43], v[42:43], 1, s[18:19]
	global_store_short v[42:43], v41, off sc1
	v_mul_f32_e32 v41, 0x3d372713, v39
	v_mul_f32_e32 v41, v39, v41
	v_fma_f32 v41, v39, v41, v39
	v_mul_f32_e32 v40, v40, v44
	v_mul_f32_e32 v41, 0xbfcc422a, v41
	v_cvt_pk_bf16_f32 v42, v40, s0
	v_add_u32_e32 v40, v14, v15
	v_mul_f32_e32 v41, 0x3fb8aa3b, v41
	v_exp_f32_e32 v43, v41
	v_ashrrev_i32_e32 v41, 31, v40
	v_lshl_add_u64 v[40:41], v[40:41], 1, s[18:19]
	global_store_short v[40:41], v42, off sc1
	v_mul_f32_e32 v41, 0x3d372713, v38
	v_mul_f32_e32 v41, v38, v41
	v_fma_f32 v41, v38, v41, v38
	v_mul_f32_e32 v41, 0xbfcc422a, v41
	v_add_f32_e32 v40, 1.0, v43
	v_mul_f32_e32 v41, 0x3fb8aa3b, v41
	v_rcp_f32_e32 v40, v40
	v_exp_f32_e32 v41, v41
	v_add_u32_e32 v20, v20, v0
	v_add_u32_e32 v14, v14, v0
	v_mul_f32_e32 v39, v39, v40
	v_add_u32_e32 v40, v13, v15
	v_add_f32_e32 v41, 1.0, v41
	v_rcp_f32_e32 v42, v41
	v_ashrrev_i32_e32 v41, 31, v40
	v_cvt_pk_bf16_f32 v39, v39, s0
	v_lshl_add_u64 v[40:41], v[40:41], 1, s[18:19]
	global_store_short v[40:41], v39, off sc1
	v_mul_f32_e32 v39, 0x3d372713, v37
	v_mul_f32_e32 v39, v37, v39
	v_fma_f32 v39, v37, v39, v37
	v_mul_f32_e32 v38, v38, v42
	v_mul_f32_e32 v39, 0xbfcc422a, v39
	v_cvt_pk_bf16_f32 v40, v38, s0
	v_add_u32_e32 v38, v12, v15
	v_mul_f32_e32 v39, 0x3fb8aa3b, v39
	v_exp_f32_e32 v41, v39
	v_ashrrev_i32_e32 v39, 31, v38
	v_lshl_add_u64 v[38:39], v[38:39], 1, s[18:19]
	global_store_short v[38:39], v40, off sc1
	v_mul_f32_e32 v39, 0x3d372713, v36
	v_mul_f32_e32 v39, v36, v39
	v_fma_f32 v39, v36, v39, v36
	v_mul_f32_e32 v39, 0xbfcc422a, v39
	v_add_f32_e32 v38, 1.0, v41
	v_mul_f32_e32 v39, 0x3fb8aa3b, v39
	v_rcp_f32_e32 v38, v38
	v_exp_f32_e32 v39, v39
	v_add_u32_e32 v12, v12, v0
	v_mul_f32_e32 v37, v37, v38
	v_add_u32_e32 v38, v11, v15
	v_add_f32_e32 v39, 1.0, v39
	v_rcp_f32_e32 v40, v39
	v_ashrrev_i32_e32 v39, 31, v38
	v_cvt_pk_bf16_f32 v37, v37, s0
	v_lshl_add_u64 v[38:39], v[38:39], 1, s[18:19]
	global_store_short v[38:39], v37, off sc1
	v_mul_f32_e32 v37, 0x3d372713, v35
	v_mul_f32_e32 v37, v35, v37
	v_fma_f32 v37, v35, v37, v35
	v_mul_f32_e32 v36, v36, v40
	v_mul_f32_e32 v37, 0xbfcc422a, v37
	v_cvt_pk_bf16_f32 v38, v36, s0
	v_add_u32_e32 v36, v10, v15
	v_mul_f32_e32 v37, 0x3fb8aa3b, v37
	v_exp_f32_e32 v39, v37
	v_ashrrev_i32_e32 v37, 31, v36
	v_lshl_add_u64 v[36:37], v[36:37], 1, s[18:19]
	global_store_short v[36:37], v38, off sc1
	v_mul_f32_e32 v37, 0x3d372713, v34
	v_mul_f32_e32 v37, v34, v37
	v_fma_f32 v37, v34, v37, v34
	v_mul_f32_e32 v37, 0xbfcc422a, v37
	v_add_f32_e32 v36, 1.0, v39
	v_mul_f32_e32 v37, 0x3fb8aa3b, v37
	v_rcp_f32_e32 v36, v36
	v_exp_f32_e32 v37, v37
	v_mul_f32_e32 v35, v35, v36
	v_add_u32_e32 v36, v7, v15
	v_add_f32_e32 v37, 1.0, v37
	v_rcp_f32_e32 v38, v37
	v_ashrrev_i32_e32 v37, 31, v36
	v_cvt_pk_bf16_f32 v35, v35, s0
	v_lshl_add_u64 v[36:37], v[36:37], 1, s[18:19]
	global_store_short v[36:37], v35, off sc1
	v_mul_f32_e32 v35, 0x3d372713, v33
	v_mul_f32_e32 v35, v33, v35
	v_fma_f32 v35, v33, v35, v33
	v_mul_f32_e32 v34, v34, v38
	v_mul_f32_e32 v35, 0xbfcc422a, v35
	v_cvt_pk_bf16_f32 v36, v34, s0
	v_add_u32_e32 v34, v6, v15
	v_mul_f32_e32 v35, 0x3fb8aa3b, v35
	v_exp_f32_e32 v37, v35
	v_ashrrev_i32_e32 v35, 31, v34
	v_lshl_add_u64 v[34:35], v[34:35], 1, s[18:19]
	global_store_short v[34:35], v36, off sc1
	v_mul_f32_e32 v35, 0x3d372713, v66
	v_mul_f32_e32 v35, v66, v35
	v_fma_f32 v35, v66, v35, v66
	v_mul_f32_e32 v35, 0xbfcc422a, v35
	v_add_f32_e32 v34, 1.0, v37
	v_mul_f32_e32 v35, 0x3fb8aa3b, v35
	v_rcp_f32_e32 v34, v34
	v_exp_f32_e32 v35, v35
	v_mul_f32_e32 v33, v33, v34
	v_add_u32_e32 v34, v3, v15
	v_add_f32_e32 v35, 1.0, v35
	v_rcp_f32_e32 v36, v35
	v_ashrrev_i32_e32 v35, 31, v34
	v_cvt_pk_bf16_f32 v33, v33, s0
	v_lshl_add_u64 v[34:35], v[34:35], 1, s[18:19]
	global_store_short v[34:35], v33, off sc1
	v_add_u32_e32 v34, v2, v15
	v_mul_f32_e32 v15, 0x3d372713, v30
	v_mul_f32_e32 v15, v30, v15
	v_fma_f32 v15, v30, v15, v30
	v_mul_f32_e32 v33, v66, v36
	v_mul_f32_e32 v15, 0xbfcc422a, v15
	v_ashrrev_i32_e32 v35, 31, v34
	v_cvt_pk_bf16_f32 v33, v33, s0
	v_mul_f32_e32 v15, 0x3fb8aa3b, v15
	v_lshl_add_u64 v[34:35], v[34:35], 1, s[18:19]
	v_exp_f32_e32 v15, v15
	global_store_short v[34:35], v33, off sc1
	v_mul_f32_e32 v33, 0x3d372713, v29
	v_mul_f32_e32 v33, v29, v33
	v_fma_f32 v33, v29, v33, v29
	v_mul_f32_e32 v33, 0xbfcc422a, v33
	v_add_f32_e32 v15, 1.0, v15
	v_mul_f32_e32 v33, 0x3fb8aa3b, v33
	v_rcp_f32_e32 v15, v15
	v_exp_f32_e32 v33, v33
	v_mul_f32_e32 v15, v30, v15
	v_add_f32_e32 v30, 1.0, v33
	v_rcp_f32_e32 v30, v30
	v_ashrrev_i32_e32 v33, 31, v32
	v_cvt_pk_bf16_f32 v15, v15, s0
	v_lshl_add_u64 v[32:33], v[32:33], 1, s[18:19]
	global_store_short v[32:33], v15, off sc1
	v_mul_f32_e32 v15, v29, v30
	v_mul_f32_e32 v29, 0x3d372713, v26
	v_mul_f32_e32 v29, v26, v29
	v_fma_f32 v29, v26, v29, v26
	v_mul_f32_e32 v29, 0xbfcc422a, v29
	v_mul_f32_e32 v29, 0x3fb8aa3b, v29
	v_exp_f32_e32 v29, v29
	v_add_u32_e32 v30, v31, v0
	v_ashrrev_i32_e32 v31, 31, v30
	v_cvt_pk_bf16_f32 v15, v15, s0
	v_lshl_add_u64 v[30:31], v[30:31], 1, s[18:19]
	global_store_short v[30:31], v15, off sc1
	v_add_f32_e32 v15, 1.0, v29
	v_mul_f32_e32 v29, 0x3d372713, v25
	v_mul_f32_e32 v29, v25, v29
	v_fma_f32 v29, v25, v29, v25
	v_mul_f32_e32 v29, 0xbfcc422a, v29
	v_mul_f32_e32 v29, 0x3fb8aa3b, v29
	v_rcp_f32_e32 v15, v15
	v_exp_f32_e32 v29, v29
	v_mul_f32_e32 v15, v26, v15
	v_add_f32_e32 v26, 1.0, v29
	v_rcp_f32_e32 v26, v26
	v_ashrrev_i32_e32 v29, 31, v28
	v_cvt_pk_bf16_f32 v15, v15, s0
	v_lshl_add_u64 v[28:29], v[28:29], 1, s[18:19]
	global_store_short v[28:29], v15, off sc1
	v_mul_f32_e32 v15, v25, v26
	v_mul_f32_e32 v25, 0x3d372713, v22
	v_mul_f32_e32 v25, v22, v25
	v_fma_f32 v25, v22, v25, v22
	v_mul_f32_e32 v25, 0xbfcc422a, v25
	v_mul_f32_e32 v25, 0x3fb8aa3b, v25
	v_exp_f32_e32 v25, v25
	v_add_u32_e32 v26, v27, v0
	v_ashrrev_i32_e32 v27, 31, v26
	v_cvt_pk_bf16_f32 v15, v15, s0
	v_lshl_add_u64 v[26:27], v[26:27], 1, s[18:19]
	global_store_short v[26:27], v15, off sc1
	v_add_f32_e32 v15, 1.0, v25
	v_mul_f32_e32 v25, 0x3d372713, v21
	v_mul_f32_e32 v25, v21, v25
	v_fma_f32 v25, v21, v25, v21
	v_mul_f32_e32 v25, 0xbfcc422a, v25
	v_mul_f32_e32 v25, 0x3fb8aa3b, v25
	v_rcp_f32_e32 v15, v15
	v_exp_f32_e32 v25, v25
	v_mul_f32_e32 v15, v22, v15
	v_add_f32_e32 v22, 1.0, v25
	v_rcp_f32_e32 v22, v22
	v_ashrrev_i32_e32 v25, 31, v24
	v_cvt_pk_bf16_f32 v15, v15, s0
	v_lshl_add_u64 v[24:25], v[24:25], 1, s[18:19]
	global_store_short v[24:25], v15, off sc1
	v_mul_f32_e32 v15, v21, v22
	v_mul_f32_e32 v21, 0x3d372713, v19
	v_mul_f32_e32 v21, v19, v21
	v_fma_f32 v21, v19, v21, v19
	v_mul_f32_e32 v21, 0xbfcc422a, v21
	v_mul_f32_e32 v21, 0x3fb8aa3b, v21
	v_exp_f32_e32 v21, v21
	v_add_u32_e32 v22, v23, v0
	v_ashrrev_i32_e32 v23, 31, v22
	v_cvt_pk_bf16_f32 v15, v15, s0
	v_lshl_add_u64 v[22:23], v[22:23], 1, s[18:19]
	global_store_short v[22:23], v15, off sc1
	v_add_f32_e32 v15, 1.0, v21
	v_mul_f32_e32 v21, 0x3d372713, v18
	v_mul_f32_e32 v21, v18, v21
	v_fma_f32 v21, v18, v21, v18
	v_mul_f32_e32 v21, 0xbfcc422a, v21
	v_mul_f32_e32 v21, 0x3fb8aa3b, v21
	v_rcp_f32_e32 v15, v15
	v_exp_f32_e32 v21, v21
	v_mul_f32_e32 v15, v19, v15
	v_add_f32_e32 v19, 1.0, v21
	v_rcp_f32_e32 v19, v19
	v_ashrrev_i32_e32 v21, 31, v20
	v_cvt_pk_bf16_f32 v15, v15, s0
	v_lshl_add_u64 v[20:21], v[20:21], 1, s[18:19]
	global_store_short v[20:21], v15, off sc1
	v_mul_f32_e32 v15, v18, v19
	v_cvt_pk_bf16_f32 v18, v15, s0
	v_mul_f32_e32 v15, 0x3d372713, v17
	v_mul_f32_e32 v15, v17, v15
	v_fma_f32 v15, v17, v15, v17
	v_mul_f32_e32 v15, 0xbfcc422a, v15
	v_mul_f32_e32 v15, 0x3fb8aa3b, v15
	v_exp_f32_e32 v19, v15
	v_ashrrev_i32_e32 v15, 31, v14
	v_lshl_add_u64 v[14:15], v[14:15], 1, s[18:19]
	global_store_short v[14:15], v18, off sc1
	v_mul_f32_e32 v15, 0x3d372713, v16
	v_mul_f32_e32 v15, v16, v15
	v_fma_f32 v15, v16, v15, v16
	v_add_f32_e32 v14, 1.0, v19
	v_mul_f32_e32 v15, 0xbfcc422a, v15
	v_rcp_f32_e32 v14, v14
	v_mul_f32_e32 v15, 0x3fb8aa3b, v15
	v_exp_f32_e32 v15, v15
	v_mul_f32_e32 v14, v17, v14
	v_cvt_pk_bf16_f32 v17, v14, s0
	v_add_u32_e32 v14, v13, v0
	v_add_f32_e32 v13, 1.0, v15
	v_rcp_f32_e32 v13, v13
	v_ashrrev_i32_e32 v15, 31, v14
	v_lshl_add_u64 v[14:15], v[14:15], 1, s[18:19]
	global_store_short v[14:15], v17, off sc1
	v_mul_f32_e32 v13, v16, v13
	v_cvt_pk_bf16_f32 v14, v13, s0
	v_mul_f32_e32 v13, 0x3d372713, v9
	v_mul_f32_e32 v13, v9, v13
	v_fma_f32 v13, v9, v13, v9
	v_mul_f32_e32 v13, 0xbfcc422a, v13
	v_mul_f32_e32 v13, 0x3fb8aa3b, v13
	v_exp_f32_e32 v15, v13
	v_ashrrev_i32_e32 v13, 31, v12
	v_lshl_add_u64 v[12:13], v[12:13], 1, s[18:19]
	global_store_short v[12:13], v14, off sc1
	v_mul_f32_e32 v13, 0x3d372713, v8
	v_mul_f32_e32 v13, v8, v13
	v_fma_f32 v13, v8, v13, v8
	v_add_f32_e32 v12, 1.0, v15
	v_mul_f32_e32 v13, 0xbfcc422a, v13
	v_rcp_f32_e32 v12, v12
	v_mul_f32_e32 v13, 0x3fb8aa3b, v13
	v_exp_f32_e32 v13, v13
	v_mul_f32_e32 v9, v9, v12
	v_add_u32_e32 v12, v11, v0
	v_add_f32_e32 v11, 1.0, v13
	v_ashrrev_i32_e32 v13, 31, v12
	v_cvt_pk_bf16_f32 v9, v9, s0
	v_rcp_f32_e32 v11, v11
	v_lshl_add_u64 v[12:13], v[12:13], 1, s[18:19]
	global_store_short v[12:13], v9, off sc1
	v_mul_f32_e32 v9, 0x3d372713, v5
	v_mul_f32_e32 v9, v5, v9
	v_fma_f32 v9, v5, v9, v5
	v_mul_f32_e32 v8, v8, v11
	v_mul_f32_e32 v9, 0xbfcc422a, v9
	v_cvt_pk_bf16_f32 v11, v8, s0
	v_add_u32_e32 v8, v10, v0
	v_mul_f32_e32 v9, 0x3fb8aa3b, v9
	v_exp_f32_e32 v10, v9
	v_ashrrev_i32_e32 v9, 31, v8
	v_lshl_add_u64 v[8:9], v[8:9], 1, s[18:19]
	global_store_short v[8:9], v11, off sc1
	v_mul_f32_e32 v9, 0x3d372713, v4
	v_mul_f32_e32 v9, v4, v9
	v_fma_f32 v9, v4, v9, v4
	v_add_f32_e32 v8, 1.0, v10
	v_mul_f32_e32 v9, 0xbfcc422a, v9
	v_rcp_f32_e32 v8, v8
	v_mul_f32_e32 v9, 0x3fb8aa3b, v9
	v_exp_f32_e32 v9, v9
	v_mul_f32_e32 v5, v5, v8
	v_add_u32_e32 v8, v7, v0
	v_add_f32_e32 v7, 1.0, v9
	v_ashrrev_i32_e32 v9, 31, v8
	v_cvt_pk_bf16_f32 v5, v5, s0
	v_rcp_f32_e32 v7, v7
	v_lshl_add_u64 v[8:9], v[8:9], 1, s[18:19]
	global_store_short v[8:9], v5, off sc1
	v_mul_f32_e32 v5, 0x3d372713, v1
	v_mul_f32_e32 v5, v1, v5
	v_fma_f32 v5, v1, v5, v1
	v_mul_f32_e32 v4, v4, v7
	v_mul_f32_e32 v5, 0xbfcc422a, v5
	v_cvt_pk_bf16_f32 v7, v4, s0
	v_add_u32_e32 v4, v6, v0
	v_mul_f32_e32 v5, 0x3fb8aa3b, v5
	v_exp_f32_e32 v6, v5
	v_ashrrev_i32_e32 v5, 31, v4
	v_lshl_add_u64 v[4:5], v[4:5], 1, s[18:19]
	global_store_short v[4:5], v7, off sc1
	v_mul_f32_e32 v5, 0x3d372713, v65
	v_mul_f32_e32 v5, v65, v5
	v_fma_f32 v5, v65, v5, v65
	v_mul_f32_e32 v5, 0xbfcc422a, v5
	v_add_f32_e32 v4, 1.0, v6
	v_mul_f32_e32 v5, 0x3fb8aa3b, v5
	v_rcp_f32_e32 v4, v4
	v_exp_f32_e32 v5, v5
	v_mul_f32_e32 v1, v1, v4
	v_add_u32_e32 v4, v3, v0
	v_add_f32_e32 v3, 1.0, v5
	v_rcp_f32_e32 v3, v3
	v_ashrrev_i32_e32 v5, 31, v4
	v_cvt_pk_bf16_f32 v1, v1, s0
	v_lshl_add_u64 v[4:5], v[4:5], 1, s[18:19]
	v_mul_f32_e32 v65, v65, v3
	v_add_u32_e32 v0, v2, v0
	global_store_short v[4:5], v1, off sc1
	s_branch .LBB0_1445
.LBB0_1454:
	s_cmp_gt_i32 s17, 20
	s_cselect_b64 s[4:5], -1, 0
	s_and_b64 s[0:1], s[0:1], s[4:5]
	s_andn2_b64 vcc, exec, s[0:1]
	s_cbranch_vccnz .LBB0_1466
	s_waitcnt vmcnt(0)
	v_or_b32_e32 v0, v201, v200
	s_movk_i32 s0, 0x3ff
	v_and_or_b32 v0, v0, s0, v199
	v_cmp_eq_u32_e32 vcc, 0, v0
	s_waitcnt lgkmcnt(0)
	s_barrier
	s_and_saveexec_b64 s[0:1], vcc
	s_cbranch_execz .LBB0_1465
	s_add_u32 s6, s14, 0x5be8c00
	s_addc_u32 s7, s15, 0
	s_lshl_b32 s3, s2, 1
	v_mov_b32_e32 v0, s3
	v_mov_b32_e32 v1, 0x9314
	global_store_short v0, v1, s[6:7] sc1
	s_cmp_lg_u32 s2, 0
	s_cbranch_scc1 .Lgbar_wait_19
	s_lshr_b32 s3, s33, 3
	s_bfm_b64 s[8:9], s3, 0
	s_cmpk_gt_u32 s33, 0x1ff
	s_cselect_b64 s[8:9], -1, s[8:9]
	s_mov_b64 exec, -1
	v_mbcnt_lo_u32_b32 v229, -1, 0
	v_mbcnt_hi_u32_b32 v229, -1, v229
	v_lshlrev_b32_e32 v229, 4, v229
	s_mov_b32 s10, 0x93149314
	s_mov_b64 exec, s[8:9]

.LBB0_1469:
	s_or_b64 exec, exec, s[30:31]
	s_waitcnt vmcnt(0)
	v_cvt_pk_bf16_f32 v4, v4, v5
	v_cvt_pk_bf16_f32 v5, v6, v7
	v_cvt_pk_bf16_f32 v6, v0, v1
	v_lshlrev_b64 v[0:1], 11, v[10:11]
	v_add_u32_e32 v18, s3, v18
	v_lshl_add_u64 v[0:1], s[20:21], 0, v[0:1]
	v_mov_b32_e32 v13, v9
	v_cmp_lt_i32_e32 vcc, s34, v18
	v_cvt_pk_bf16_f32 v7, v2, v3
	v_lshl_add_u64 v[0:1], v[0:1], 0, v[12:13]
	s_or_b64 s[22:23], vcc, s[22:23]
	v_add_u32_e32 v19, s10, v19
	global_store_dwordx4 v[0:1], v[4:7], off sc1
	s_andn2_b64 exec, exec, s[22:23]
	s_cbranch_execz .LBB0_1478

.LBB0_1479:
	s_cmp_gt_i32 s17, 21
	s_cselect_b64 s[4:5], -1, 0
	s_and_b64 s[0:1], s[0:1], s[4:5]
	s_andn2_b64 vcc, exec, s[0:1]
	s_cbranch_vccnz .LBB0_1491
	s_waitcnt vmcnt(0)
	v_or_b32_e32 v0, v201, v200
	s_movk_i32 s0, 0x3ff
	v_and_or_b32 v0, v0, s0, v199
	v_cmp_eq_u32_e32 vcc, 0, v0
	s_waitcnt lgkmcnt(0)
	s_barrier
	s_and_saveexec_b64 s[0:1], vcc
	s_cbranch_execz .LBB0_1490
	s_add_u32 s6, s14, 0x5be8c00
	s_addc_u32 s7, s15, 0
	s_lshl_b32 s3, s2, 1
	v_mov_b32_e32 v0, s3
	v_mov_b32_e32 v1, 0x9315
	global_store_short v0, v1, s[6:7] sc1
	s_cmp_lg_u32 s2, 0
	s_cbranch_scc1 .Lgbar_wait_20
	s_lshr_b32 s3, s33, 3
	s_bfm_b64 s[8:9], s3, 0
	s_cmpk_gt_u32 s33, 0x1ff
	s_cselect_b64 s[8:9], -1, s[8:9]
	s_mov_b64 exec, -1
	v_mbcnt_lo_u32_b32 v229, -1, 0
	v_mbcnt_hi_u32_b32 v229, -1, v229
	v_lshlrev_b32_e32 v229, 4, v229
	s_mov_b32 s10, 0x93159315
	s_mov_b64 exec, s[8:9]

.LBB0_1494:
	s_ashr_i32 s0, s3, 31
	s_lshr_b32 s0, s0, 24
	s_add_i32 s0, s3, s0
	s_ashr_i32 s1, s0, 8
	s_and_b32 s0, s0, 0xffffff00
	s_sub_i32 s4, s3, s0
	s_ashr_i32 s0, s4, 31
	s_lshr_b32 s0, s0, 29
	s_add_i32 s0, s4, s0
	s_and_b32 s5, s0, -8
	s_lshl_b32 s1, s1, 3
	s_sub_i32 s60, s4, s5
	s_ashr_i32 s46, s0, 3
	s_add_i32 s60, s60, s1
	s_lshl_b32 s61, s46, 6
	s_lshl_b32 s4, s60, 7
	s_lshl_b32 s46, s46, 7
	s_ashr_i32 s5, s4, 31
	s_ashr_i32 s47, s46, 31
	s_lshl_b64 s[4:5], s[4:5], 11
	s_lshl_b64 s[48:49], s[46:47], 8
	s_add_u32 s1, s8, s4
	s_addc_u32 s5, s9, s5
	s_and_b32 s4, s46, 0x700
	s_add_u32 s4, s1, s4
	s_addc_u32 s5, s5, 0
	s_add_u32 s46, s10, s48
	v_readfirstlane_b32 s1, v87
	s_addc_u32 s47, s11, s49
	v_lshl_add_u64 v[0:1], s[4:5], 0, v[64:65]
	s_mov_b32 m0, s1
	v_readfirstlane_b32 s1, v88
	v_lshl_add_u64 v[2:3], s[46:47], 0, v[66:67]
	global_load_lds_dwordx4 v[0:1], off
	s_mov_b32 m0, s1
	v_readfirstlane_b32 s1, v89
	global_load_lds_dwordx4 v[2:3], off
	v_lshl_add_u64 v[4:5], v[0:1], 0, s[18:19]
	s_mov_b32 m0, s1
	v_readfirstlane_b32 s1, v90
	global_load_lds_dwordx4 v[4:5], off
	v_lshl_add_u64 v[4:5], v[2:3], 0, s[20:21]
	s_mov_b32 m0, s1
	v_readfirstlane_b32 s1, v91
	global_load_lds_dwordx4 v[4:5], off
	v_lshl_add_u64 v[4:5], v[0:1], 0, s[22:23]
	s_mov_b32 m0, s1
	v_readfirstlane_b32 s1, v92
	global_load_lds_dwordx4 v[4:5], off
	v_lshl_add_u64 v[4:5], v[2:3], 0, s[24:25]
	s_mov_b32 m0, s1
	v_readfirstlane_b32 s1, v93
	global_load_lds_dwordx4 v[4:5], off
	v_lshl_add_u64 v[4:5], v[0:1], 0, s[26:27]
	s_mov_b32 m0, s1
	v_readfirstlane_b32 s1, v94
	global_load_lds_dwordx4 v[4:5], off
	v_lshl_add_u64 v[4:5], v[2:3], 0, s[28:29]
	s_mov_b32 m0, s1
	v_readfirstlane_b32 s1, v95
	global_load_lds_dwordx4 v[4:5], off
	v_lshl_add_u64 v[4:5], v[0:1], 0, s[30:31]
	s_mov_b32 m0, s1
	v_readfirstlane_b32 s1, v96
	s_waitcnt vmcnt(0)
	s_waitcnt vmcnt(0) lgkmcnt(0)
	s_barrier
	global_load_lds_dwordx4 v[4:5], off
	v_lshl_add_u64 v[4:5], v[2:3], 0, s[30:31]
	s_mov_b32 m0, s1
	v_readfirstlane_b32 s1, v97
	global_load_lds_dwordx4 v[4:5], off
	v_lshl_add_u64 v[4:5], v[0:1], 0, s[34:35]
	s_mov_b32 m0, s1
	v_readfirstlane_b32 s1, v98
	global_load_lds_dwordx4 v[4:5], off
	v_lshl_add_u64 v[4:5], v[2:3], 0, s[36:37]
	s_mov_b32 m0, s1
	v_readfirstlane_b32 s1, v99
	global_load_lds_dwordx4 v[4:5], off
	v_lshl_add_u64 v[4:5], v[0:1], 0, s[38:39]
	s_mov_b32 m0, s1
	v_readfirstlane_b32 s1, v100
	global_load_lds_dwordx4 v[4:5], off
	v_lshl_add_u64 v[4:5], v[2:3], 0, s[40:41]
	s_mov_b32 m0, s1
	v_readfirstlane_b32 s1, v101
	global_load_lds_dwordx4 v[4:5], off
	v_lshl_add_u64 v[0:1], v[0:1], 0, s[42:43]
	s_mov_b32 m0, s1
	v_readfirstlane_b32 s1, v102
	global_load_lds_dwordx4 v[0:1], off
	v_lshl_add_u64 v[0:1], v[2:3], 0, s[44:45]
	s_mov_b32 m0, s1
	s_nop 0
	global_load_lds_dwordx4 v[0:1], off
	ds_read_b128 v[0:3], v103
	ds_read_b128 v[4:7], v104 offset:16384
	ds_read_b128 v[8:11], v104 offset:20480
	ds_read_b128 v[12:15], v104 offset:24576
	ds_read_b128 v[118:121], v104 offset:28672
	ds_read_b128 v[122:125], v105
	ds_read_b128 v[126:129], v106 offset:16384
	ds_read_b128 v[130:133], v106 offset:20480
	ds_read_b128 v[134:137], v106 offset:24576
	ds_read_b128 v[138:141], v106 offset:28672
	s_setprio 1
	s_waitcnt lgkmcnt(0)
	v_mfma_f32_32x32x16_bf16 v[16:31], v[0:3], v[4:7], 0
	v_mfma_f32_32x32x16_bf16 v[32:47], v[0:3], v[8:11], 0
	v_mfma_f32_32x32x16_bf16 v[48:63], v[0:3], v[12:15], 0
	v_mfma_f32_32x32x16_bf16 v[0:15], v[0:3], v[118:121], 0
	s_setprio 0
	ds_read_b128 v[118:121], v107
	ds_read_b128 v[142:145], v108 offset:16384
	ds_read_b128 v[146:149], v108 offset:20480
	ds_read_b128 v[150:153], v108 offset:24576
	ds_read_b128 v[154:157], v108 offset:28672
	s_setprio 1
	v_mfma_f32_32x32x16_bf16 v[16:31], v[122:125], v[126:129], v[16:31]
	v_mfma_f32_32x32x16_bf16 v[32:47], v[122:125], v[130:133], v[32:47]
	v_mfma_f32_32x32x16_bf16 v[48:63], v[122:125], v[134:137], v[48:63]
	v_mfma_f32_32x32x16_bf16 v[0:15], v[122:125], v[138:141], v[0:15]
	s_setprio 0
	ds_read_b128 v[122:125], v109
	ds_read_b128 v[126:129], v110 offset:16384
	ds_read_b128 v[130:133], v110 offset:20480
	ds_read_b128 v[134:137], v110 offset:24576
	ds_read_b128 v[138:141], v110 offset:28672
	s_setprio 1
	s_waitcnt lgkmcnt(0)
	v_mfma_f32_32x32x16_bf16 v[16:31], v[118:121], v[142:145], v[16:31]
	v_mfma_f32_32x32x16_bf16 v[32:47], v[118:121], v[146:149], v[32:47]
	v_mfma_f32_32x32x16_bf16 v[48:63], v[118:121], v[150:153], v[48:63]
	v_mfma_f32_32x32x16_bf16 v[0:15], v[118:121], v[154:157], v[0:15]
	s_setprio 0
	s_setprio 1
	v_mfma_f32_32x32x16_bf16 v[16:31], v[122:125], v[126:129], v[16:31]
	v_mfma_f32_32x32x16_bf16 v[32:47], v[122:125], v[130:133], v[32:47]
	v_mfma_f32_32x32x16_bf16 v[48:63], v[122:125], v[134:137], v[48:63]
	v_mfma_f32_32x32x16_bf16 v[0:15], v[122:125], v[138:141], v[0:15]
	s_setprio 0
	s_waitcnt vmcnt(0)
	s_waitcnt vmcnt(0)
	s_barrier
	ds_read_b128 v[118:121], v103 offset:32768
	ds_read_b128 v[122:125], v104 offset:49152
	ds_read_b128 v[126:129], v104 offset:53248
	ds_read_b128 v[130:133], v104 offset:57344
	ds_read_b128 v[134:137], v104 offset:61440
	ds_read_b128 v[138:141], v105 offset:32768
	ds_read_b128 v[142:145], v106 offset:49152
	ds_read_b128 v[146:149], v106 offset:53248
	ds_read_b128 v[150:153], v106 offset:57344
	ds_read_b128 v[154:157], v106 offset:61440
	s_setprio 1
	s_waitcnt lgkmcnt(8)
	v_mfma_f32_32x32x16_bf16 v[16:31], v[118:121], v[122:125], v[16:31]
	s_waitcnt lgkmcnt(7)
	v_mfma_f32_32x32x16_bf16 v[32:47], v[118:121], v[126:129], v[32:47]
	s_waitcnt lgkmcnt(6)
	v_mfma_f32_32x32x16_bf16 v[48:63], v[118:121], v[130:133], v[48:63]
	s_waitcnt lgkmcnt(5)
	v_mfma_f32_32x32x16_bf16 v[0:15], v[118:121], v[134:137], v[0:15]
	s_setprio 0
	ds_read_b128 v[118:121], v107 offset:32768
	ds_read_b128 v[122:125], v108 offset:49152
	ds_read_b128 v[126:129], v108 offset:53248
	ds_read_b128 v[130:133], v108 offset:57344
	ds_read_b128 v[134:137], v108 offset:61440
	s_setprio 1
	s_waitcnt lgkmcnt(8)
	v_mfma_f32_32x32x16_bf16 v[16:31], v[138:141], v[142:145], v[16:31]
	s_waitcnt lgkmcnt(7)
	v_mfma_f32_32x32x16_bf16 v[32:47], v[138:141], v[146:149], v[32:47]
	s_waitcnt lgkmcnt(6)
	v_mfma_f32_32x32x16_bf16 v[48:63], v[138:141], v[150:153], v[48:63]
	s_waitcnt lgkmcnt(5)
	v_mfma_f32_32x32x16_bf16 v[0:15], v[138:141], v[154:157], v[0:15]
	s_setprio 0
	ds_read_b128 v[138:141], v109 offset:32768
	ds_read_b128 v[142:145], v110 offset:49152
	ds_read_b128 v[146:149], v110 offset:53248
	ds_read_b128 v[150:153], v110 offset:57344
	ds_read_b128 v[154:157], v110 offset:61440
	s_setprio 1
	s_waitcnt lgkmcnt(8)
	v_mfma_f32_32x32x16_bf16 v[16:31], v[118:121], v[122:125], v[16:31]
	s_waitcnt lgkmcnt(7)
	v_mfma_f32_32x32x16_bf16 v[32:47], v[118:121], v[126:129], v[32:47]
	s_waitcnt lgkmcnt(6)
	v_mfma_f32_32x32x16_bf16 v[48:63], v[118:121], v[130:133], v[48:63]
	s_waitcnt lgkmcnt(5)
	v_mfma_f32_32x32x16_bf16 v[0:15], v[118:121], v[134:137], v[0:15]
	s_setprio 0
	s_setprio 1
	s_waitcnt lgkmcnt(3)
	v_mfma_f32_32x32x16_bf16 v[16:31], v[138:141], v[142:145], v[16:31]
	s_waitcnt lgkmcnt(2)
	v_mfma_f32_32x32x16_bf16 v[32:47], v[138:141], v[146:149], v[32:47]
	s_waitcnt lgkmcnt(1)
	v_mfma_f32_32x32x16_bf16 v[48:63], v[138:141], v[150:153], v[48:63]
	s_waitcnt lgkmcnt(0)
	v_mfma_f32_32x32x16_bf16 v[0:15], v[138:141], v[154:157], v[0:15]
	s_setprio 0
	ds_read_b128 v[118:121], v111
	s_ashr_i32 s46, s0, 7
	s_lshl_b32 s0, s46, 11
	s_ashr_i32 s1, s0, 31
	s_lshl_b64 s[0:1], s[0:1], 2
	s_waitcnt lgkmcnt(0)
	v_readfirstlane_b32 s4, v118
	v_readfirstlane_b32 s5, v119
	s_add_u32 s0, s4, s0
	s_addc_u32 s1, s5, s1
	s_lshl_b32 s4, s46, 10
	s_ashr_i32 s5, s4, 31
	v_readfirstlane_b32 s47, v120
	s_lshl_b64 s[4:5], s[4:5], 2
	v_readfirstlane_b32 s48, v121
	s_add_u32 s4, s47, s4
	s_addc_u32 s5, s48, s5
	s_ashr_i32 s47, s46, 31
	s_lshl_b64 s[46:47], s[46:47], 25
	s_add_u32 s48, s50, s46
	s_addc_u32 s49, s51, s47
	s_add_u32 s46, s52, s46
	s_addc_u32 s47, s53, s47
	s_and_b32 s61, s61, 0x3c0
	v_or_b32_e32 v124, s61, v70
	v_lshlrev_b32_e32 v68, 2, v124
	global_load_dword v119, v68, s[4:5]
	global_load_dword v122, v68, s[4:5] offset:128
	global_load_dword v117, v68, s[0:1]
	global_load_dword v118, v68, s[0:1] offset:128
	v_lshl_add_u64 v[120:121], s[0:1], 0, v[68:69]
	v_add_co_u32_e32 v120, vcc, s54, v120
	s_waitcnt vmcnt(3)
	v_mul_f32_e32 v68, 0xbfb8aa3b, v119
	v_exp_f32_e32 v125, v68
	s_waitcnt vmcnt(2)
	v_mul_f32_e32 v119, 0xbfb8aa3b, v122
	v_exp_f32_e32 v128, v119
	v_addc_co_u32_e32 v121, vcc, 0, v121, vcc
	v_add_f32_e32 v126, 1.0, v125
	global_load_dword v119, v[120:121], off
	global_load_dword v68, v[120:121], off offset:128
	v_frexp_mant_f32_e32 v130, v126
	v_cvt_f64_f32_e32 v[120:121], v126
	v_add_f32_e32 v127, 1.0, v128
	v_add_f32_e32 v129, -1.0, v126
	v_frexp_exp_i32_f64_e32 v120, v[120:121]
	v_cmp_gt_f32_e32 vcc, s55, v130
	v_add_f32_e32 v131, -1.0, v127
	v_frexp_mant_f32_e32 v132, v127
	v_cvt_f64_f32_e32 v[122:123], v127
	v_sub_f32_e32 v133, v129, v126
	v_subbrev_co_u32_e32 v120, vcc, 0, v120, vcc
	v_sub_f32_e32 v129, v125, v129
	v_sub_f32_e32 v121, v131, v127
	v_frexp_exp_i32_f64_e32 v122, v[122:123]
	v_add_f32_e32 v123, 1.0, v133
	v_cmp_gt_f32_e32 vcc, s55, v132
	v_sub_f32_e32 v131, v128, v131
	v_add_f32_e32 v121, 1.0, v121
	v_subbrev_co_u32_e32 v122, vcc, 0, v122, vcc
	v_add_f32_e32 v123, v129, v123
	v_sub_u32_e32 v129, 0, v120
	v_cvt_f32_i32_e32 v120, v120
	v_add_f32_e32 v121, v131, v121
	v_sub_u32_e32 v130, 0, v122
	v_ldexp_f32 v126, v126, v129
	v_ldexp_f32 v123, v123, v129
	v_ldexp_f32 v127, v127, v130
	v_ldexp_f32 v121, v121, v130
	v_add_f32_e32 v129, -1.0, v126
	v_add_f32_e32 v130, 1.0, v126
	v_add_f32_e32 v131, 1.0, v129
	v_add_f32_e32 v132, -1.0, v130
	v_sub_f32_e32 v131, v126, v131
	v_sub_f32_e32 v126, v126, v132
	v_mul_f32_e32 v132, 0x3f317218, v120
	v_add_f32_e32 v131, v123, v131
	v_add_f32_e32 v123, v123, v126
	v_fma_f32 v126, v120, s56, -v132
	v_add_f32_e32 v133, v129, v131
	v_add_f32_e32 v134, v130, v123
	v_fmac_f32_e32 v126, 0xb102e308, v120
	v_sub_f32_e32 v120, v133, v129
	v_sub_f32_e32 v129, v134, v130
	v_rcp_f32_e32 v130, v134
	v_add_f32_e32 v135, v132, v126
	v_sub_f32_e32 v123, v123, v129
	v_sub_f32_e32 v129, v135, v132
	v_sub_f32_e32 v126, v126, v129
	v_mul_f32_e32 v129, v133, v130
	v_sub_f32_e32 v120, v131, v120
	v_mul_f32_e32 v131, v134, v129
	v_fma_f32 v132, v129, v134, -v131
	v_fmac_f32_e32 v132, v129, v123
	v_add_f32_e32 v136, v131, v132
	v_sub_f32_e32 v137, v133, v136
	v_sub_f32_e32 v131, v136, v131
	v_sub_f32_e32 v133, v133, v137
	v_sub_f32_e32 v131, v131, v132
	v_sub_f32_e32 v132, v133, v136
	v_add_f32_e32 v120, v120, v132
	v_add_f32_e32 v120, v131, v120
	v_add_f32_e32 v131, v137, v120
	v_mul_f32_e32 v132, v130, v131
	v_sub_f32_e32 v133, v137, v131
	v_mul_f32_e32 v136, v134, v132
	v_add_f32_e32 v120, v120, v133
	v_add_f32_e32 v133, v129, v132
	v_fma_f32 v134, v132, v134, -v136
	v_sub_f32_e32 v129, v133, v129
	v_fmac_f32_e32 v134, v132, v123
	v_sub_f32_e32 v123, v132, v129
	v_add_f32_e32 v129, v136, v134
	v_sub_f32_e32 v132, v129, v136
	v_sub_f32_e32 v136, v131, v129
	v_sub_f32_e32 v131, v131, v136
	v_sub_f32_e32 v129, v131, v129
	v_sub_f32_e32 v132, v132, v134
	v_add_f32_e32 v120, v120, v129
	v_add_f32_e32 v120, v132, v120
	v_add_f32_e32 v120, v136, v120
	v_mul_f32_e32 v120, v130, v120
	v_add_f32_e32 v120, v123, v120
	v_add_f32_e32 v123, v133, v120
	v_mul_f32_e32 v129, v123, v123
	v_fmamk_f32 v132, v129, 0x3e9b6dac, v112
	v_sub_f32_e32 v130, v123, v133
	v_ldexp_f32 v131, v123, 1
	v_mul_f32_e32 v123, v123, v129
	v_fmaak_f32 v129, v129, v132, 0x3f2aaada
	v_mul_f32_e32 v123, v123, v129
	v_add_f32_e32 v129, v131, v123
	v_sub_f32_e32 v120, v120, v130
	v_sub_f32_e32 v130, v129, v131
	v_ldexp_f32 v120, v120, 1
	v_sub_f32_e32 v123, v123, v130
	v_add_f32_e32 v120, v120, v123
	v_add_f32_e32 v123, v129, v120
	v_sub_f32_e32 v129, v123, v129
	v_add_f32_e32 v130, v135, v123
	v_sub_f32_e32 v120, v120, v129
	v_sub_f32_e32 v129, v130, v135
	v_sub_f32_e32 v131, v130, v129
	v_sub_f32_e32 v123, v123, v129
	v_add_f32_e32 v129, v126, v120
	v_sub_f32_e32 v131, v135, v131
	v_sub_f32_e32 v132, v129, v126
	v_add_f32_e32 v123, v123, v131
	v_sub_f32_e32 v131, v129, v132
	v_sub_f32_e32 v120, v120, v132
	v_sub_f32_e32 v126, v126, v131
	v_add_f32_e32 v123, v129, v123
	v_add_f32_e32 v120, v120, v126
	v_add_f32_e32 v126, v130, v123
	v_sub_f32_e32 v129, v126, v130
	v_sub_f32_e32 v123, v123, v129
	v_add_f32_e32 v120, v120, v123
	v_add_f32_e32 v120, v126, v120
	v_cmp_neq_f32_e32 vcc, s57, v125
	v_add_f32_e32 v123, -1.0, v127
	v_add_f32_e32 v129, 1.0, v127
	v_cndmask_b32_e32 v120, v114, v120, vcc
	v_cmp_ngt_f32_e32 vcc, -1.0, v125
	v_add_f32_e32 v130, -1.0, v129
	v_cvt_f32_i32_e32 v122, v122
	v_cndmask_b32_e32 v120, v115, v120, vcc
	v_cmp_neq_f32_e32 vcc, -1.0, v125
	s_waitcnt vmcnt(3)
	v_add_f32_e32 v16, v16, v117
	v_mul_f32_e32 v16, 0xbfb8aa3b, v16
	v_cndmask_b32_e32 v120, v116, v120, vcc
	v_cmp_lt_f32_e64 vcc, |v125|, s58
	v_exp_f32_e32 v16, v16
	v_cmp_lt_f32_e64 s[0:1], |v128|, s58
	v_cndmask_b32_e32 v120, v120, v125, vcc
	v_add_f32_e32 v125, 1.0, v123
	v_sub_f32_e32 v125, v127, v125
	v_sub_f32_e32 v127, v127, v130
	v_add_f32_e32 v125, v121, v125
	v_add_f32_e32 v121, v121, v127
	v_add_f32_e32 v127, v129, v121
	v_rcp_f32_e32 v130, v127
	v_add_f32_e32 v126, v123, v125
	v_sub_f32_e32 v123, v126, v123
	v_sub_f32_e32 v123, v125, v123
	v_sub_f32_e32 v125, v127, v129
	v_sub_f32_e32 v121, v121, v125
	v_mul_f32_e32 v125, v126, v130
	v_mul_f32_e32 v129, v127, v125
	v_fma_f32 v131, v125, v127, -v129
	v_fmac_f32_e32 v131, v125, v121
	v_add_f32_e32 v132, v129, v131
	v_sub_f32_e32 v133, v126, v132
	v_sub_f32_e32 v126, v126, v133
	v_sub_f32_e32 v129, v132, v129
	v_sub_f32_e32 v126, v126, v132
	v_add_f32_e32 v123, v123, v126
	v_sub_f32_e32 v126, v129, v131
	v_add_f32_e32 v123, v126, v123
	v_add_f32_e32 v126, v133, v123
	v_mul_f32_e32 v129, v130, v126
	v_mul_f32_e32 v131, v127, v129
	v_fma_f32 v127, v129, v127, -v131
	v_fmac_f32_e32 v127, v129, v121
	v_sub_f32_e32 v121, v133, v126
	v_add_f32_e32 v121, v123, v121
	v_add_f32_e32 v123, v131, v127
	v_sub_f32_e32 v132, v126, v123
	v_sub_f32_e32 v126, v126, v132
	v_sub_f32_e32 v131, v123, v131
	v_sub_f32_e32 v123, v126, v123
	v_add_f32_e32 v121, v121, v123
	v_sub_f32_e32 v123, v131, v127
	v_add_f32_e32 v121, v123, v121
	v_add_f32_e32 v123, v125, v129
	v_add_f32_e32 v121, v132, v121
	v_sub_f32_e32 v125, v123, v125
	v_mul_f32_e32 v121, v130, v121
	v_sub_f32_e32 v125, v129, v125
	v_add_f32_e32 v121, v125, v121
	v_mul_f32_e32 v129, 0x3f317218, v122
	v_add_f32_e32 v125, v123, v121
	v_fma_f32 v130, v122, s56, -v129
	v_mul_f32_e32 v126, v125, v125
	v_fmac_f32_e32 v130, 0xb102e308, v122
	v_fmamk_f32 v127, v126, 0x3e9b6dac, v112
	v_sub_f32_e32 v122, v125, v123
	v_add_f32_e32 v131, v129, v130
	v_fmaak_f32 v127, v126, v127, 0x3f2aaada
	v_sub_f32_e32 v121, v121, v122
	v_sub_f32_e32 v122, v131, v129
	v_mul_f32_e32 v123, v125, v126
	v_sub_f32_e32 v129, v130, v122
	v_ldexp_f32 v122, v125, 1
	v_mul_f32_e32 v123, v123, v127
	v_add_f32_e32 v125, v122, v123
	v_sub_f32_e32 v122, v125, v122
	v_ldexp_f32 v121, v121, 1
	v_sub_f32_e32 v122, v123, v122
	v_add_f32_e32 v121, v121, v122
	v_add_f32_e32 v130, v125, v121
	v_sub_f32_e32 v122, v130, v125
	v_sub_f32_e32 v132, v121, v122
	v_lshl_or_b32 v121, s60, 17, v124
	v_add_u32_e32 v122, v121, v71
	v_ashrrev_i32_e32 v123, 31, v122
	v_lshlrev_b64 v[124:125], 1, v[122:123]
	v_lshl_add_u64 v[126:127], s[8:9], 0, v[124:125]
	global_load_ushort v126, v[126:127], off
	v_add_f32_e32 v123, v131, v130
	v_sub_f32_e32 v127, v123, v131
	v_sub_f32_e32 v133, v123, v127
	v_sub_f32_e32 v131, v131, v133
	v_sub_f32_e32 v127, v130, v127
	v_add_f32_e32 v130, v129, v132
	v_add_f32_e32 v127, v127, v131
	v_sub_f32_e32 v131, v130, v129
	v_sub_f32_e32 v133, v130, v131
	v_add_f32_e32 v127, v130, v127
	v_sub_f32_e32 v129, v129, v133
	v_sub_f32_e32 v131, v132, v131
	v_add_f32_e32 v130, v123, v127
	v_or_b32_e32 v122, 32, v122
	v_add_f32_e32 v129, v131, v129
	v_sub_f32_e32 v131, v130, v123
	v_ashrrev_i32_e32 v123, 31, v122
	v_lshl_add_u64 v[122:123], v[122:123], 1, s[8:9]
	global_load_ushort v122, v[122:123], off
	v_add_f32_e32 v16, 1.0, v16
	v_rcp_f32_e32 v16, v16
	v_mul_f32_e32 v120, 0xc1000000, v120
	v_sub_f32_e32 v123, v127, v131
	v_add_f32_e32 v123, v129, v123
	v_mul_f32_e32 v127, v16, v120
	s_waitcnt vmcnt(4)
	v_add_f32_e32 v16, v32, v118
	v_mul_f32_e32 v16, 0xbfb8aa3b, v16
	v_add_f32_e32 v32, v127, v127
	v_exp_f32_e32 v16, v16
	v_mul_f32_e32 v32, 0x3fb8aa3b, v32
	v_exp_f32_e32 v32, v32
	v_add_f32_e32 v123, v130, v123
	v_cmp_neq_f32_e32 vcc, s57, v128
	v_add_f32_e32 v16, 1.0, v16
	v_rcp_f32_e32 v129, v16
	v_cndmask_b32_e32 v123, v114, v123, vcc
	v_cmp_ngt_f32_e32 vcc, -1.0, v128
	v_sub_f32_e32 v16, 1.0, v32
	v_max_f32_e32 v16, 0, v16
	v_cndmask_b32_e32 v123, v115, v123, vcc
	v_cmp_neq_f32_e32 vcc, -1.0, v128
	v_mul_f32_e32 v32, 0x4f800000, v16
	s_waitcnt vmcnt(3)
	v_add_f32_e32 v48, v48, v119
	v_cndmask_b32_e32 v123, v116, v123, vcc
	v_cmp_gt_f32_e32 vcc, s59, v16
	v_mul_f32_e32 v48, 0xbfb8aa3b, v48
	v_exp_f32_e32 v48, v48
	v_cndmask_b32_e32 v32, v16, v32, vcc
	v_sqrt_f32_e32 v130, v32
	v_cndmask_b32_e64 v16, v123, v128, s[0:1]
	v_mul_f32_e32 v16, 0xc1000000, v16
	v_mul_f32_e32 v128, v129, v16
	v_add_u32_e32 v123, -1, v130
	v_fma_f32 v129, -v123, v130, v32
	v_cmp_ge_f32_e64 s[0:1], 0, v129
	v_add_u32_e32 v129, 1, v130
	v_add_f32_e32 v48, 1.0, v48
	v_cndmask_b32_e64 v123, v130, v123, s[0:1]
	v_fma_f32 v130, -v129, v130, v32
	v_cmp_lt_f32_e64 s[0:1], 0, v130
	v_rcp_f32_e32 v48, v48
	s_waitcnt vmcnt(2)
	v_add_f32_e32 v0, v0, v68
	v_cndmask_b32_e64 v123, v123, v129, s[0:1]
	v_mul_f32_e32 v129, 0x37800000, v123
	v_cndmask_b32_e32 v123, v123, v129, vcc
	v_add_f32_e32 v129, v128, v128
	v_mul_f32_e32 v129, 0x3fb8aa3b, v129
	v_exp_f32_e32 v129, v129
	v_cmp_class_f32_e32 vcc, v32, v113
	v_mul_f32_e32 v0, 0xbfb8aa3b, v0
	v_exp_f32_e32 v0, v0
	v_cndmask_b32_e32 v32, v123, v32, vcc
	v_sub_f32_e32 v123, 1.0, v129
	v_max_f32_e32 v123, 0, v123
	v_mul_f32_e32 v129, 0x4f800000, v123
	v_cmp_gt_f32_e32 vcc, s59, v123
	v_mul_f32_e32 v32, v48, v32
	v_add_f32_e32 v0, 1.0, v0
	v_cndmask_b32_e32 v123, v123, v129, vcc
	v_sqrt_f32_e32 v129, v123
	s_waitcnt vmcnt(1)
	v_lshlrev_b32_e32 v48, 16, v126
	v_mul_f32_e32 v32, v32, v48
	v_rcp_f32_e32 v0, v0
	v_add_u32_e32 v48, -1, v129
	v_fma_f32 v126, -v48, v129, v123
	v_cmp_ge_f32_e64 s[0:1], 0, v126
	v_add_u32_e32 v126, 1, v129
	v_add_f32_e32 v17, v17, v117
	v_cndmask_b32_e64 v48, v129, v48, s[0:1]
	v_fma_f32 v129, -v126, v129, v123
	v_cmp_lt_f32_e64 s[0:1], 0, v129
	v_mul_f32_e32 v17, 0xbfb8aa3b, v17
	v_exp_f32_e32 v17, v17
	v_cndmask_b32_e64 v48, v48, v126, s[0:1]
	v_mul_f32_e32 v126, 0x37800000, v48
	v_cndmask_b32_e32 v48, v48, v126, vcc
	v_cmp_class_f32_e32 vcc, v123, v113
	v_cvt_pk_bf16_f32 v32, v32, s0
	v_add_f32_e32 v17, 1.0, v17
	v_cndmask_b32_e32 v48, v48, v123, vcc
	v_mul_f32_e32 v0, v0, v48
	s_waitcnt vmcnt(0)
	v_lshlrev_b32_e32 v48, 16, v122
	v_mul_f32_e32 v0, v0, v48
	v_cvt_pk_bf16_f32 v48, v127, s0
	v_lshl_add_u64 v[122:123], s[48:49], 0, v[124:125]
	global_store_short v[122:123], v48, off sc1
	v_cvt_pk_bf16_f32 v48, v128, s0
	global_store_short v[122:123], v48, off offset:64 sc1
	v_lshl_add_u64 v[122:123], s[46:47], 0, v[124:125]
	v_cvt_pk_bf16_f32 v0, v0, s0
	global_store_short v[122:123], v32, off sc1
	global_store_short v[122:123], v0, off offset:64 sc1
	v_add_u32_e32 v122, v121, v72
	v_ashrrev_i32_e32 v123, 31, v122
	v_lshlrev_b64 v[124:125], 1, v[122:123]
	v_lshl_add_u64 v[126:127], s[8:9], 0, v[124:125]
	global_load_ushort v0, v[126:127], off
	v_or_b32_e32 v122, 32, v122
	v_ashrrev_i32_e32 v123, 31, v122
	v_lshl_add_u64 v[122:123], v[122:123], 1, s[8:9]
	global_load_ushort v32, v[122:123], off
	v_rcp_f32_e32 v17, v17
	v_add_f32_e32 v33, v33, v118
	v_mul_f32_e32 v33, 0xbfb8aa3b, v33
	v_exp_f32_e32 v33, v33
	v_mul_f32_e32 v17, v17, v120
	v_add_f32_e32 v48, v17, v17
	v_mul_f32_e32 v48, 0x3fb8aa3b, v48
	v_exp_f32_e32 v48, v48
	v_add_f32_e32 v33, 1.0, v33
	v_rcp_f32_e32 v33, v33
	v_add_f32_e32 v49, v49, v119
	v_sub_f32_e32 v48, 1.0, v48
	v_max_f32_e32 v48, 0, v48
	v_mul_f32_e32 v122, 0x4f800000, v48
	v_cmp_gt_f32_e32 vcc, s59, v48
	v_mul_f32_e32 v33, v33, v16
	v_mul_f32_e32 v49, 0xbfb8aa3b, v49
	v_cndmask_b32_e32 v48, v48, v122, vcc
	v_sqrt_f32_e32 v122, v48
	v_exp_f32_e32 v49, v49
	v_add_f32_e32 v1, v1, v68
	v_mul_f32_e32 v1, 0xbfb8aa3b, v1
	v_add_u32_e32 v123, -1, v122
	v_fma_f32 v126, -v123, v122, v48
	v_cmp_ge_f32_e64 s[0:1], 0, v126
	v_add_u32_e32 v126, 1, v122
	v_add_f32_e32 v49, 1.0, v49
	v_cndmask_b32_e64 v123, v122, v123, s[0:1]
	v_fma_f32 v122, -v126, v122, v48
	v_cmp_lt_f32_e64 s[0:1], 0, v122
	v_rcp_f32_e32 v49, v49
	v_exp_f32_e32 v1, v1
	v_cndmask_b32_e64 v122, v123, v126, s[0:1]
	v_mul_f32_e32 v123, 0x37800000, v122
	v_cndmask_b32_e32 v122, v122, v123, vcc
	v_add_f32_e32 v123, v33, v33
	v_mul_f32_e32 v123, 0x3fb8aa3b, v123
	v_exp_f32_e32 v123, v123
	v_cmp_class_f32_e32 vcc, v48, v113
	v_add_f32_e32 v1, 1.0, v1
	v_rcp_f32_e32 v1, v1
	v_cndmask_b32_e32 v48, v122, v48, vcc
	v_sub_f32_e32 v122, 1.0, v123
	v_max_f32_e32 v122, 0, v122
	v_mul_f32_e32 v123, 0x4f800000, v122
	v_cmp_gt_f32_e32 vcc, s59, v122
	v_mul_f32_e32 v48, v49, v48
	v_add_f32_e32 v2, v2, v68
	v_cndmask_b32_e32 v122, v122, v123, vcc
	v_sqrt_f32_e32 v123, v122
	v_mul_f32_e32 v2, 0xbfb8aa3b, v2
	v_exp_f32_e32 v2, v2
	v_add_f32_e32 v3, v3, v68
	v_mul_f32_e32 v3, 0xbfb8aa3b, v3
	v_exp_f32_e32 v3, v3
	v_add_f32_e32 v2, 1.0, v2
	v_rcp_f32_e32 v2, v2
	v_add_f32_e32 v3, 1.0, v3
	v_rcp_f32_e32 v3, v3
	s_waitcnt vmcnt(1)
	v_lshlrev_b32_e32 v0, 16, v0
	v_mul_f32_e32 v48, v48, v0
	v_add_u32_e32 v0, -1, v123
	v_fma_f32 v49, -v0, v123, v122
	v_cmp_ge_f32_e64 s[0:1], 0, v49
	v_add_u32_e32 v49, 1, v123
	s_nop 0
	v_cndmask_b32_e64 v0, v123, v0, s[0:1]
	v_fma_f32 v123, -v49, v123, v122
	v_cmp_lt_f32_e64 s[0:1], 0, v123
	s_nop 1
	v_cndmask_b32_e64 v0, v0, v49, s[0:1]
	v_mul_f32_e32 v49, 0x37800000, v0
	v_cndmask_b32_e32 v0, v0, v49, vcc
	v_cmp_class_f32_e32 vcc, v122, v113
	v_cvt_pk_bf16_f32 v17, v17, s0
	s_nop 0
	v_cndmask_b32_e32 v0, v0, v122, vcc
	v_mul_f32_e32 v0, v1, v0
	s_waitcnt vmcnt(0)
	v_lshlrev_b32_e32 v1, 16, v32
	v_mul_f32_e32 v32, v0, v1
	v_lshl_add_u64 v[0:1], s[48:49], 0, v[124:125]
	global_store_short v[0:1], v17, off sc1
	v_cvt_pk_bf16_f32 v17, v33, s0
	global_store_short v[0:1], v17, off offset:64 sc1
	v_cvt_pk_bf16_f32 v17, v48, s0
	v_lshl_add_u64 v[0:1], s[46:47], 0, v[124:125]
	global_store_short v[0:1], v17, off sc1
	v_cvt_pk_bf16_f32 v17, v32, s0
	global_store_short v[0:1], v17, off offset:64 sc1
	v_add_u32_e32 v0, v121, v73
	v_ashrrev_i32_e32 v1, 31, v0
	v_lshlrev_b64 v[32:33], 1, v[0:1]
	v_lshl_add_u64 v[48:49], s[8:9], 0, v[32:33]
	global_load_ushort v17, v[48:49], off
	v_or_b32_e32 v0, 32, v0
	v_ashrrev_i32_e32 v1, 31, v0
	v_lshl_add_u64 v[0:1], v[0:1], 1, s[8:9]
	global_load_ushort v0, v[0:1], off
	v_add_f32_e32 v1, v18, v117
	v_mul_f32_e32 v1, 0xbfb8aa3b, v1
	v_exp_f32_e32 v1, v1
	v_add_f32_e32 v18, v34, v118
	v_mul_f32_e32 v18, 0xbfb8aa3b, v18
	v_exp_f32_e32 v18, v18
	v_add_f32_e32 v1, 1.0, v1
	v_rcp_f32_e32 v1, v1
	v_add_f32_e32 v18, 1.0, v18
	v_rcp_f32_e32 v18, v18
	v_mul_f32_e32 v1, v1, v120
	v_add_f32_e32 v34, v1, v1
	v_mul_f32_e32 v34, 0x3fb8aa3b, v34
	v_exp_f32_e32 v34, v34
	v_mul_f32_e32 v18, v18, v16
	v_sub_f32_e32 v34, 1.0, v34
	v_max_f32_e32 v34, 0, v34
	v_mul_f32_e32 v48, 0x4f800000, v34
	v_cmp_gt_f32_e32 vcc, s59, v34
	s_waitcnt vmcnt(1)
	v_lshlrev_b32_e32 v17, 16, v17
	v_cndmask_b32_e32 v34, v34, v48, vcc
	v_sqrt_f32_e32 v48, v34
	s_waitcnt vmcnt(0)
	v_lshlrev_b32_e32 v0, 16, v0
	v_add_u32_e32 v49, -1, v48
	v_fma_f32 v122, -v49, v48, v34
	v_cmp_ge_f32_e64 s[0:1], 0, v122
	v_add_u32_e32 v122, 1, v48
	s_nop 0
	v_cndmask_b32_e64 v49, v48, v49, s[0:1]
	v_fma_f32 v48, -v122, v48, v34
	v_cmp_lt_f32_e64 s[0:1], 0, v48
	s_nop 1
	v_cndmask_b32_e64 v48, v49, v122, s[0:1]
	v_mul_f32_e32 v49, 0x37800000, v48
	v_cndmask_b32_e32 v48, v48, v49, vcc
	v_add_f32_e32 v49, v50, v119
	v_add_f32_e32 v50, v18, v18
	v_mul_f32_e32 v49, 0xbfb8aa3b, v49
	v_mul_f32_e32 v50, 0x3fb8aa3b, v50
	v_exp_f32_e32 v49, v49
	v_exp_f32_e32 v50, v50
	v_cmp_class_f32_e32 vcc, v34, v113
	s_nop 1
	v_cndmask_b32_e32 v34, v48, v34, vcc
	v_add_f32_e32 v48, 1.0, v49
	v_sub_f32_e32 v49, 1.0, v50
	v_max_f32_e32 v49, 0, v49
	v_mul_f32_e32 v50, 0x4f800000, v49
	v_cmp_gt_f32_e32 vcc, s59, v49
	v_rcp_f32_e32 v48, v48
	s_nop 0
	v_cndmask_b32_e32 v49, v49, v50, vcc
	v_sqrt_f32_e32 v50, v49
	v_mul_f32_e32 v34, v48, v34
	v_mul_f32_e32 v17, v34, v17
	v_add_u32_e32 v34, -1, v50
	v_fma_f32 v48, -v34, v50, v49
	v_cmp_ge_f32_e64 s[0:1], 0, v48
	v_add_u32_e32 v48, 1, v50
	s_nop 0
	v_cndmask_b32_e64 v34, v50, v34, s[0:1]
	v_fma_f32 v50, -v48, v50, v49
	v_cmp_lt_f32_e64 s[0:1], 0, v50
	s_nop 1
	v_cndmask_b32_e64 v34, v34, v48, s[0:1]
	v_mul_f32_e32 v48, 0x37800000, v34
	v_cndmask_b32_e32 v34, v34, v48, vcc
	v_cmp_class_f32_e32 vcc, v49, v113
	v_cvt_pk_bf16_f32 v18, v18, s0
	v_cvt_pk_bf16_f32 v17, v17, s0
	v_cndmask_b32_e32 v34, v34, v49, vcc
	v_mul_f32_e32 v2, v2, v34
	v_mul_f32_e32 v2, v2, v0
	v_cvt_pk_bf16_f32 v34, v1, s0
	v_lshl_add_u64 v[0:1], s[48:49], 0, v[32:33]
	global_store_short v[0:1], v34, off sc1
	global_store_short v[0:1], v18, off offset:64 sc1
	v_lshl_add_u64 v[0:1], s[46:47], 0, v[32:33]
	v_cvt_pk_bf16_f32 v2, v2, s0
	global_store_short v[0:1], v17, off sc1
	global_store_short v[0:1], v2, off offset:64 sc1
	v_add_u32_e32 v0, v121, v74
	v_ashrrev_i32_e32 v1, 31, v0
	v_lshlrev_b64 v[32:33], 1, v[0:1]
	v_lshl_add_u64 v[48:49], s[8:9], 0, v[32:33]
	global_load_ushort v2, v[48:49], off
	v_or_b32_e32 v0, 32, v0
	v_ashrrev_i32_e32 v1, 31, v0
	v_lshl_add_u64 v[0:1], v[0:1], 1, s[8:9]
	global_load_ushort v0, v[0:1], off
	v_add_f32_e32 v1, v19, v117
	v_mul_f32_e32 v1, 0xbfb8aa3b, v1
	v_exp_f32_e32 v1, v1
	v_add_f32_e32 v17, v35, v118
	v_mul_f32_e32 v17, 0xbfb8aa3b, v17
	v_exp_f32_e32 v17, v17
	v_add_f32_e32 v1, 1.0, v1
	v_rcp_f32_e32 v1, v1
	v_add_f32_e32 v17, 1.0, v17
	v_rcp_f32_e32 v17, v17
	v_mul_f32_e32 v1, v1, v120
	v_add_f32_e32 v18, v1, v1
	v_mul_f32_e32 v18, 0x3fb8aa3b, v18
	v_exp_f32_e32 v18, v18
	v_mul_f32_e32 v17, v17, v16
	v_sub_f32_e32 v18, 1.0, v18
	v_max_f32_e32 v18, 0, v18
	v_mul_f32_e32 v19, 0x4f800000, v18
	v_cmp_gt_f32_e32 vcc, s59, v18
	s_waitcnt vmcnt(1)
	v_lshlrev_b32_e32 v2, 16, v2
	v_cndmask_b32_e32 v18, v18, v19, vcc
	v_sqrt_f32_e32 v19, v18
	s_waitcnt vmcnt(0)
	v_lshlrev_b32_e32 v0, 16, v0
	v_add_u32_e32 v34, -1, v19
	v_fma_f32 v35, -v34, v19, v18
	v_cmp_ge_f32_e64 s[0:1], 0, v35
	v_add_u32_e32 v35, 1, v19
	s_nop 0
	v_cndmask_b32_e64 v34, v19, v34, s[0:1]
	v_fma_f32 v19, -v35, v19, v18
	v_cmp_lt_f32_e64 s[0:1], 0, v19
	s_nop 1
	v_cndmask_b32_e64 v19, v34, v35, s[0:1]
	v_mul_f32_e32 v34, 0x37800000, v19
	v_cndmask_b32_e32 v19, v19, v34, vcc
	v_add_f32_e32 v34, v51, v119
	v_add_f32_e32 v35, v17, v17
	v_mul_f32_e32 v34, 0xbfb8aa3b, v34
	v_mul_f32_e32 v35, 0x3fb8aa3b, v35
	v_exp_f32_e32 v34, v34
	v_exp_f32_e32 v35, v35
	v_cmp_class_f32_e32 vcc, v18, v113
	s_nop 1
	v_cndmask_b32_e32 v18, v19, v18, vcc
	v_add_f32_e32 v19, 1.0, v34
	v_sub_f32_e32 v34, 1.0, v35
	v_max_f32_e32 v34, 0, v34
	v_mul_f32_e32 v35, 0x4f800000, v34
	v_cmp_gt_f32_e32 vcc, s59, v34
	v_rcp_f32_e32 v19, v19
	s_nop 0
	v_cndmask_b32_e32 v34, v34, v35, vcc
	v_sqrt_f32_e32 v35, v34
	v_mul_f32_e32 v18, v19, v18
	v_mul_f32_e32 v2, v18, v2
	v_add_u32_e32 v18, -1, v35
	v_fma_f32 v19, -v18, v35, v34
	v_cmp_ge_f32_e64 s[0:1], 0, v19
	v_add_u32_e32 v19, 1, v35
	s_nop 0
	v_cndmask_b32_e64 v18, v35, v18, s[0:1]
	v_fma_f32 v35, -v19, v35, v34
	v_cmp_lt_f32_e64 s[0:1], 0, v35
	s_nop 1
	v_cndmask_b32_e64 v18, v18, v19, s[0:1]
	v_mul_f32_e32 v19, 0x37800000, v18
	v_cndmask_b32_e32 v18, v18, v19, vcc
	v_cmp_class_f32_e32 vcc, v34, v113
	v_cvt_pk_bf16_f32 v17, v17, s0
	v_cvt_pk_bf16_f32 v2, v2, s0
	v_cndmask_b32_e32 v18, v18, v34, vcc
	v_mul_f32_e32 v3, v3, v18
	v_mul_f32_e32 v3, v3, v0
	v_cvt_pk_bf16_f32 v18, v1, s0
	v_lshl_add_u64 v[0:1], s[48:49], 0, v[32:33]
	global_store_short v[0:1], v18, off sc1
	global_store_short v[0:1], v17, off offset:64 sc1
	v_lshl_add_u64 v[0:1], s[46:47], 0, v[32:33]
	global_store_short v[0:1], v2, off sc1
	v_cvt_pk_bf16_f32 v2, v3, s0
	global_store_short v[0:1], v2, off offset:64 sc1
	v_add_u32_e32 v0, v121, v75
	v_ashrrev_i32_e32 v1, 31, v0
	v_lshlrev_b64 v[2:3], 1, v[0:1]
	v_or_b32_e32 v0, 32, v0
	v_lshl_add_u64 v[18:19], s[8:9], 0, v[2:3]
	v_ashrrev_i32_e32 v1, 31, v0
	v_lshl_add_u64 v[0:1], v[0:1], 1, s[8:9]
	global_load_ushort v17, v[18:19], off
	s_nop 0
	global_load_ushort v18, v[0:1], off
	v_add_f32_e32 v0, v20, v117
	v_add_f32_e32 v1, v36, v118
	v_mul_f32_e32 v0, 0xbfb8aa3b, v0
	v_mul_f32_e32 v1, 0xbfb8aa3b, v1
	v_exp_f32_e32 v20, v0
	v_exp_f32_e32 v32, v1
	v_lshl_add_u64 v[0:1], s[48:49], 0, v[2:3]
	v_add_f32_e32 v19, v52, v119
	v_add_f32_e32 v20, 1.0, v20
	v_add_f32_e32 v32, 1.0, v32
	v_rcp_f32_e32 v20, v20
	v_rcp_f32_e32 v32, v32
	v_add_f32_e32 v4, v4, v68
	v_mul_f32_e32 v19, 0xbfb8aa3b, v19
	v_mul_f32_e32 v20, v20, v120
	v_mul_f32_e32 v32, v32, v16
	v_add_f32_e32 v33, v20, v20
	v_add_f32_e32 v34, v32, v32
	v_mul_f32_e32 v33, 0x3fb8aa3b, v33
	v_mul_f32_e32 v34, 0x3fb8aa3b, v34
	v_exp_f32_e32 v33, v33
	v_exp_f32_e32 v34, v34
	v_cvt_pk_bf16_f32 v20, v20, s0
	global_store_short v[0:1], v20, off sc1
	v_sub_f32_e32 v20, 1.0, v33
	v_sub_f32_e32 v33, 1.0, v34
	v_max_f32_e32 v20, 0, v20
	v_max_f32_e32 v33, 0, v33
	v_mul_f32_e32 v34, 0x4f800000, v20
	v_cmp_gt_f32_e32 vcc, s59, v20
	v_cvt_pk_bf16_f32 v32, v32, s0
	v_mul_f32_e32 v35, 0x4f800000, v33
	v_cndmask_b32_e32 v20, v20, v34, vcc
	v_cmp_gt_f32_e64 s[0:1], s59, v33
	v_sqrt_f32_e32 v34, v20
	v_mul_f32_e32 v4, 0xbfb8aa3b, v4
	v_cndmask_b32_e64 v33, v33, v35, s[0:1]
	v_sqrt_f32_e32 v35, v33
	global_store_short v[0:1], v32, off offset:64 sc1
	v_add_u32_e32 v0, -1, v34
	v_exp_f32_e32 v19, v19
	v_exp_f32_e32 v4, v4
	v_add_u32_e32 v32, -1, v35
	v_fma_f32 v48, -v0, v34, v20
	v_add_u32_e32 v1, 1, v34
	v_fma_f32 v50, -v32, v35, v33
	v_cmp_ge_f32_e64 s[4:5], 0, v48
	v_add_u32_e32 v36, 1, v35
	v_fma_f32 v49, -v1, v34, v20
	v_cndmask_b32_e64 v0, v34, v0, s[4:5]
	v_cmp_ge_f32_e64 s[4:5], 0, v50
	v_fma_f32 v51, -v36, v35, v33
	v_add_f32_e32 v19, 1.0, v19
	v_cndmask_b32_e64 v32, v35, v32, s[4:5]
	v_cmp_lt_f32_e64 s[4:5], 0, v49
	v_add_f32_e32 v4, 1.0, v4
	v_rcp_f32_e32 v19, v19
	v_cndmask_b32_e64 v0, v0, v1, s[4:5]
	v_cmp_lt_f32_e64 s[4:5], 0, v51
	v_rcp_f32_e32 v4, v4
	v_lshl_add_u64 v[2:3], s[46:47], 0, v[2:3]
	v_cndmask_b32_e64 v1, v32, v36, s[4:5]
	v_mul_f32_e32 v32, 0x37800000, v0
	v_mul_f32_e32 v34, 0x37800000, v1
	v_cndmask_b32_e32 v0, v0, v32, vcc
	v_cmp_class_f32_e32 vcc, v20, v113
	v_cndmask_b32_e64 v1, v1, v34, s[0:1]
	v_add_f32_e32 v5, v5, v68
	v_cndmask_b32_e32 v0, v0, v20, vcc
	v_cmp_class_f32_e32 vcc, v33, v113
	v_mul_f32_e32 v0, v19, v0
	v_mul_f32_e32 v5, 0xbfb8aa3b, v5
	v_cndmask_b32_e32 v1, v1, v33, vcc
	v_mul_f32_e32 v1, v4, v1
	v_exp_f32_e32 v5, v5
	v_add_f32_e32 v6, v6, v68
	v_mul_f32_e32 v6, 0xbfb8aa3b, v6
	v_exp_f32_e32 v6, v6
	s_waitcnt vmcnt(3)
	v_lshlrev_b32_e32 v4, 16, v17
	s_waitcnt vmcnt(2)
	v_lshlrev_b32_e32 v17, 16, v18
	v_mul_f32_e32 v0, v0, v4
	v_mul_f32_e32 v1, v1, v17
	v_cvt_pk_bf16_f32 v0, v0, s0
	v_cvt_pk_bf16_f32 v1, v1, s0
	global_store_short v[2:3], v0, off sc1
	global_store_short v[2:3], v1, off offset:64 sc1
	v_add_u32_e32 v0, v121, v76
	v_ashrrev_i32_e32 v1, 31, v0
	v_lshlrev_b64 v[2:3], 1, v[0:1]
	v_or_b32_e32 v0, 32, v0
	v_lshl_add_u64 v[18:19], s[8:9], 0, v[2:3]
	v_ashrrev_i32_e32 v1, 31, v0
	v_lshl_add_u64 v[0:1], v[0:1], 1, s[8:9]
	global_load_ushort v4, v[18:19], off
	global_load_ushort v17, v[0:1], off
	v_add_f32_e32 v0, v21, v117
	v_add_f32_e32 v1, v37, v118
	v_mul_f32_e32 v0, 0xbfb8aa3b, v0
	v_mul_f32_e32 v1, 0xbfb8aa3b, v1
	v_exp_f32_e32 v19, v0
	v_exp_f32_e32 v20, v1
	v_add_f32_e32 v18, v53, v119
	v_mul_f32_e32 v18, 0xbfb8aa3b, v18
	v_add_f32_e32 v19, 1.0, v19
	v_add_f32_e32 v20, 1.0, v20
	v_rcp_f32_e32 v19, v19
	v_rcp_f32_e32 v20, v20
	v_exp_f32_e32 v18, v18
	v_add_f32_e32 v5, 1.0, v5
	v_mul_f32_e32 v19, v19, v120
	v_mul_f32_e32 v20, v20, v16
	v_add_f32_e32 v21, v19, v19
	v_add_f32_e32 v32, v20, v20
	v_mul_f32_e32 v21, 0x3fb8aa3b, v21
	v_mul_f32_e32 v32, 0x3fb8aa3b, v32
	v_exp_f32_e32 v21, v21
	v_exp_f32_e32 v32, v32
	v_add_f32_e32 v18, 1.0, v18
	v_rcp_f32_e32 v18, v18
	v_sub_f32_e32 v21, 1.0, v21
	v_sub_f32_e32 v32, 1.0, v32
	v_max_f32_e32 v21, 0, v21
	v_max_f32_e32 v32, 0, v32
	v_mul_f32_e32 v33, 0x4f800000, v21
	v_cmp_gt_f32_e32 vcc, s59, v21
	v_mul_f32_e32 v34, 0x4f800000, v32
	v_cmp_gt_f32_e64 s[0:1], s59, v32
	v_cndmask_b32_e32 v21, v21, v33, vcc
	v_sqrt_f32_e32 v33, v21
	v_cndmask_b32_e64 v32, v32, v34, s[0:1]
	v_sqrt_f32_e32 v34, v32
	v_rcp_f32_e32 v5, v5
	v_add_u32_e32 v35, -1, v33
	v_fma_f32 v49, -v35, v33, v21
	v_add_u32_e32 v37, -1, v34
	v_add_u32_e32 v36, 1, v33
	v_fma_f32 v51, -v37, v34, v32
	v_cmp_ge_f32_e64 s[4:5], 0, v49
	v_add_u32_e32 v48, 1, v34
	v_fma_f32 v50, -v36, v33, v21
	v_cndmask_b32_e64 v33, v33, v35, s[4:5]
	v_cmp_ge_f32_e64 s[4:5], 0, v51
	v_fma_f32 v52, -v48, v34, v32
	v_lshl_add_u64 v[0:1], s[48:49], 0, v[2:3]
	v_cndmask_b32_e64 v34, v34, v37, s[4:5]
	v_cmp_lt_f32_e64 s[4:5], 0, v50
	v_cvt_pk_bf16_f32 v19, v19, s0
	global_store_short v[0:1], v19, off sc1
	v_cndmask_b32_e64 v33, v33, v36, s[4:5]
	v_cmp_lt_f32_e64 s[4:5], 0, v52
	v_mul_f32_e32 v35, 0x37800000, v33
	v_cndmask_b32_e32 v33, v33, v35, vcc
	v_cndmask_b32_e64 v34, v34, v48, s[4:5]
	v_mul_f32_e32 v36, 0x37800000, v34
	v_cmp_class_f32_e32 vcc, v21, v113
	v_cndmask_b32_e64 v34, v34, v36, s[0:1]
	v_add_f32_e32 v6, 1.0, v6
	v_cndmask_b32_e32 v21, v33, v21, vcc
	v_cmp_class_f32_e32 vcc, v32, v113
	v_mul_f32_e32 v18, v18, v21
	v_rcp_f32_e32 v6, v6
	v_cndmask_b32_e32 v32, v34, v32, vcc
	v_mul_f32_e32 v5, v5, v32
	v_add_f32_e32 v7, v7, v68
	v_mul_f32_e32 v7, 0xbfb8aa3b, v7
	v_exp_f32_e32 v7, v7
	s_waitcnt vmcnt(2)
	v_lshlrev_b32_e32 v4, 16, v4
	s_waitcnt vmcnt(1)
	v_lshlrev_b32_e32 v17, 16, v17
	v_mul_f32_e32 v4, v18, v4
	v_mul_f32_e32 v5, v5, v17
	v_cvt_pk_bf16_f32 v17, v20, s0
	global_store_short v[0:1], v17, off offset:64 sc1
	v_cvt_pk_bf16_f32 v4, v4, s0
	v_lshl_add_u64 v[0:1], s[46:47], 0, v[2:3]
	v_cvt_pk_bf16_f32 v2, v5, s0
	global_store_short v[0:1], v4, off sc1
	global_store_short v[0:1], v2, off offset:64 sc1
	v_add_u32_e32 v0, v121, v77
	v_ashrrev_i32_e32 v1, 31, v0
	v_lshlrev_b64 v[2:3], 1, v[0:1]
	v_or_b32_e32 v0, 32, v0
	v_ashrrev_i32_e32 v1, 31, v0
	v_lshl_add_u64 v[4:5], s[8:9], 0, v[2:3]
	v_lshl_add_u64 v[0:1], v[0:1], 1, s[8:9]
	global_load_ushort v4, v[4:5], off
	v_add_f32_e32 v17, v54, v119
	global_load_ushort v0, v[0:1], off
	v_add_f32_e32 v1, v22, v117
	v_add_f32_e32 v5, v38, v118
	v_mul_f32_e32 v1, 0xbfb8aa3b, v1
	v_mul_f32_e32 v5, 0xbfb8aa3b, v5
	v_exp_f32_e32 v1, v1
	v_exp_f32_e32 v5, v5
	v_mul_f32_e32 v17, 0xbfb8aa3b, v17
	v_exp_f32_e32 v17, v17
	v_add_f32_e32 v1, 1.0, v1
	v_add_f32_e32 v5, 1.0, v5
	v_rcp_f32_e32 v1, v1
	v_rcp_f32_e32 v5, v5
	v_add_f32_e32 v17, 1.0, v17
	v_rcp_f32_e32 v17, v17
	v_mul_f32_e32 v1, v1, v120
	v_mul_f32_e32 v5, v5, v16
	v_add_f32_e32 v18, v1, v1
	v_add_f32_e32 v19, v5, v5
	v_mul_f32_e32 v18, 0x3fb8aa3b, v18
	v_mul_f32_e32 v19, 0x3fb8aa3b, v19
	v_exp_f32_e32 v18, v18
	v_exp_f32_e32 v19, v19
	v_sub_f32_e32 v18, 1.0, v18
	v_sub_f32_e32 v19, 1.0, v19
	v_max_f32_e32 v18, 0, v18
	v_max_f32_e32 v19, 0, v19
	v_mul_f32_e32 v20, 0x4f800000, v18
	v_cmp_gt_f32_e32 vcc, s59, v18
	v_mul_f32_e32 v21, 0x4f800000, v19
	v_cmp_gt_f32_e64 s[0:1], s59, v19
	v_cndmask_b32_e32 v18, v18, v20, vcc
	v_sqrt_f32_e32 v20, v18
	v_cndmask_b32_e64 v19, v19, v21, s[0:1]
	v_sqrt_f32_e32 v21, v19
	v_cvt_pk_bf16_f32 v5, v5, s0
	v_add_u32_e32 v22, -1, v20
	v_fma_f32 v35, -v22, v20, v18
	v_add_u32_e32 v33, -1, v21
	v_add_u32_e32 v32, 1, v20
	v_fma_f32 v37, -v33, v21, v19
	v_cmp_ge_f32_e64 s[4:5], 0, v35
	v_add_u32_e32 v34, 1, v21
	v_fma_f32 v36, -v32, v20, v18
	v_cndmask_b32_e64 v20, v20, v22, s[4:5]
	v_cmp_ge_f32_e64 s[4:5], 0, v37
	v_fma_f32 v38, -v34, v21, v19
	s_waitcnt vmcnt(1)
	v_lshlrev_b32_e32 v4, 16, v4
	v_cndmask_b32_e64 v21, v21, v33, s[4:5]
	v_cmp_lt_f32_e64 s[4:5], 0, v36
	s_waitcnt vmcnt(0)
	v_lshlrev_b32_e32 v0, 16, v0
	v_cndmask_b32_e64 v20, v20, v32, s[4:5]
	v_cmp_lt_f32_e64 s[4:5], 0, v38
	v_mul_f32_e32 v22, 0x37800000, v20
	v_cndmask_b32_e32 v20, v20, v22, vcc
	v_cndmask_b32_e64 v21, v21, v34, s[4:5]
	v_mul_f32_e32 v32, 0x37800000, v21
	v_cmp_class_f32_e32 vcc, v18, v113
	v_cndmask_b32_e64 v21, v21, v32, s[0:1]
	s_nop 0
	v_cndmask_b32_e32 v18, v20, v18, vcc
	v_cmp_class_f32_e32 vcc, v19, v113
	v_mul_f32_e32 v17, v17, v18
	v_mul_f32_e32 v4, v17, v4
	v_cndmask_b32_e32 v19, v21, v19, vcc
	v_mul_f32_e32 v6, v6, v19
	v_mul_f32_e32 v6, v6, v0
	v_cvt_pk_bf16_f32 v17, v1, s0
	v_lshl_add_u64 v[0:1], s[48:49], 0, v[2:3]
	global_store_short v[0:1], v17, off sc1
	global_store_short v[0:1], v5, off offset:64 sc1
	v_cvt_pk_bf16_f32 v4, v4, s0
	v_lshl_add_u64 v[0:1], s[46:47], 0, v[2:3]
	v_cvt_pk_bf16_f32 v2, v6, s0
	global_store_short v[0:1], v4, off sc1
	global_store_short v[0:1], v2, off offset:64 sc1
	v_add_u32_e32 v0, v121, v78
	v_ashrrev_i32_e32 v1, 31, v0
	v_lshlrev_b64 v[2:3], 1, v[0:1]
	v_lshl_add_u64 v[4:5], s[8:9], 0, v[2:3]
	global_load_ushort v4, v[4:5], off
	v_or_b32_e32 v0, 32, v0
	v_ashrrev_i32_e32 v1, 31, v0
	v_lshl_add_u64 v[0:1], v[0:1], 1, s[8:9]
	global_load_ushort v0, v[0:1], off
	v_add_f32_e32 v1, v23, v117
	v_add_f32_e32 v5, v39, v118
	v_mul_f32_e32 v1, 0xbfb8aa3b, v1
	v_mul_f32_e32 v5, 0xbfb8aa3b, v5
	v_exp_f32_e32 v1, v1
	v_exp_f32_e32 v5, v5
	v_add_f32_e32 v6, v55, v119
	v_mul_f32_e32 v6, 0xbfb8aa3b, v6
	v_add_f32_e32 v1, 1.0, v1
	v_add_f32_e32 v5, 1.0, v5
	v_rcp_f32_e32 v1, v1
	v_rcp_f32_e32 v5, v5
	v_exp_f32_e32 v6, v6
	v_mul_f32_e32 v1, v1, v120
	v_mul_f32_e32 v5, v5, v16
	v_add_f32_e32 v17, v1, v1
	v_add_f32_e32 v18, v5, v5
	v_mul_f32_e32 v17, 0x3fb8aa3b, v17
	v_mul_f32_e32 v18, 0x3fb8aa3b, v18
	v_exp_f32_e32 v17, v17
	v_exp_f32_e32 v18, v18
	v_add_f32_e32 v6, 1.0, v6
	v_rcp_f32_e32 v6, v6
	v_sub_f32_e32 v17, 1.0, v17
	v_sub_f32_e32 v18, 1.0, v18
	v_max_f32_e32 v17, 0, v17
	v_max_f32_e32 v18, 0, v18
	v_mul_f32_e32 v19, 0x4f800000, v17
	v_cmp_gt_f32_e32 vcc, s59, v17
	v_mul_f32_e32 v20, 0x4f800000, v18
	v_cmp_gt_f32_e64 s[0:1], s59, v18
	v_cndmask_b32_e32 v17, v17, v19, vcc
	v_sqrt_f32_e32 v19, v17
	v_cndmask_b32_e64 v18, v18, v20, s[0:1]
	v_sqrt_f32_e32 v20, v18
	v_cvt_pk_bf16_f32 v5, v5, s0
	v_add_u32_e32 v21, -1, v19
	v_fma_f32 v33, -v21, v19, v17
	v_add_u32_e32 v23, -1, v20
	v_add_u32_e32 v22, 1, v19
	v_fma_f32 v35, -v23, v20, v18
	v_cmp_ge_f32_e64 s[4:5], 0, v33
	v_add_u32_e32 v32, 1, v20
	v_fma_f32 v34, -v22, v19, v17
	v_cndmask_b32_e64 v19, v19, v21, s[4:5]
	v_cmp_ge_f32_e64 s[4:5], 0, v35
	v_fma_f32 v36, -v32, v20, v18
	s_waitcnt vmcnt(1)
	v_lshlrev_b32_e32 v4, 16, v4
	v_cndmask_b32_e64 v20, v20, v23, s[4:5]
	v_cmp_lt_f32_e64 s[4:5], 0, v34
	s_waitcnt vmcnt(0)
	v_lshlrev_b32_e32 v0, 16, v0
	v_cndmask_b32_e64 v19, v19, v22, s[4:5]
	v_mul_f32_e32 v21, 0x37800000, v19
	v_cndmask_b32_e32 v19, v19, v21, vcc
	v_cmp_class_f32_e32 vcc, v17, v113
	v_cmp_lt_f32_e64 s[4:5], 0, v36
	s_nop 0
	v_cndmask_b32_e32 v17, v19, v17, vcc
	v_mul_f32_e32 v6, v6, v17
	v_mul_f32_e32 v4, v6, v4
	v_add_f32_e32 v6, 1.0, v7
	v_cndmask_b32_e64 v20, v20, v32, s[4:5]
	v_rcp_f32_e32 v6, v6
	v_mul_f32_e32 v22, 0x37800000, v20
	v_cndmask_b32_e64 v7, v20, v22, s[0:1]
	v_cmp_class_f32_e32 vcc, v18, v113
	v_cvt_pk_bf16_f32 v4, v4, s0
	s_nop 0
	v_cndmask_b32_e32 v7, v7, v18, vcc
	v_mul_f32_e32 v6, v6, v7
	v_mul_f32_e32 v6, v6, v0
	v_cvt_pk_bf16_f32 v7, v1, s0
	v_lshl_add_u64 v[0:1], s[48:49], 0, v[2:3]
	global_store_short v[0:1], v7, off sc1
	global_store_short v[0:1], v5, off offset:64 sc1
	v_lshl_add_u64 v[0:1], s[46:47], 0, v[2:3]
	v_cvt_pk_bf16_f32 v2, v6, s0
	global_store_short v[0:1], v4, off sc1
	global_store_short v[0:1], v2, off offset:64 sc1
	v_add_u32_e32 v0, v121, v79
	v_ashrrev_i32_e32 v1, 31, v0
	v_lshlrev_b64 v[2:3], 1, v[0:1]
	v_or_b32_e32 v0, 32, v0
	v_lshl_add_u64 v[4:5], s[8:9], 0, v[2:3]
	v_ashrrev_i32_e32 v1, 31, v0
	v_lshl_add_u64 v[0:1], v[0:1], 1, s[8:9]
	global_load_ushort v4, v[4:5], off
	s_nop 0
	global_load_ushort v5, v[0:1], off
	v_add_f32_e32 v0, v24, v117
	v_add_f32_e32 v1, v40, v118
	v_mul_f32_e32 v0, 0xbfb8aa3b, v0
	v_add_f32_e32 v7, v8, v68
	v_mul_f32_e32 v1, 0xbfb8aa3b, v1
	v_exp_f32_e32 v8, v0
	v_exp_f32_e32 v17, v1
	v_lshl_add_u64 v[0:1], s[48:49], 0, v[2:3]
	v_add_f32_e32 v6, v56, v119
	v_add_f32_e32 v8, 1.0, v8
	v_add_f32_e32 v17, 1.0, v17
	v_rcp_f32_e32 v8, v8
	v_rcp_f32_e32 v17, v17
	v_mul_f32_e32 v6, 0xbfb8aa3b, v6
	v_mul_f32_e32 v7, 0xbfb8aa3b, v7
	v_mul_f32_e32 v8, v8, v120
	v_mul_f32_e32 v17, v17, v16
	v_add_f32_e32 v18, v8, v8
	v_add_f32_e32 v19, v17, v17
	v_mul_f32_e32 v18, 0x3fb8aa3b, v18
	v_mul_f32_e32 v19, 0x3fb8aa3b, v19
	v_exp_f32_e32 v18, v18
	v_exp_f32_e32 v19, v19
	v_cvt_pk_bf16_f32 v8, v8, s0
	global_store_short v[0:1], v8, off sc1
	v_sub_f32_e32 v8, 1.0, v18
	v_sub_f32_e32 v18, 1.0, v19
	v_max_f32_e32 v8, 0, v8
	v_max_f32_e32 v18, 0, v18
	v_mul_f32_e32 v19, 0x4f800000, v8
	v_cmp_gt_f32_e32 vcc, s59, v8
	v_cvt_pk_bf16_f32 v17, v17, s0
	v_mul_f32_e32 v20, 0x4f800000, v18
	v_cndmask_b32_e32 v8, v8, v19, vcc
	v_cmp_gt_f32_e64 s[0:1], s59, v18
	v_sqrt_f32_e32 v19, v8
	v_exp_f32_e32 v6, v6
	v_cndmask_b32_e64 v18, v18, v20, s[0:1]
	v_sqrt_f32_e32 v20, v18
	global_store_short v[0:1], v17, off offset:64 sc1
	v_add_u32_e32 v0, -1, v19
	v_exp_f32_e32 v7, v7
	v_add_u32_e32 v17, -1, v20
	v_fma_f32 v22, -v0, v19, v8
	v_add_u32_e32 v1, 1, v19
	v_fma_f32 v24, -v17, v20, v18
	v_cmp_ge_f32_e64 s[4:5], 0, v22
	v_add_u32_e32 v21, 1, v20
	v_fma_f32 v23, -v1, v19, v8
	v_cndmask_b32_e64 v0, v19, v0, s[4:5]
	v_cmp_ge_f32_e64 s[4:5], 0, v24
	v_add_f32_e32 v6, 1.0, v6
	v_fma_f32 v32, -v21, v20, v18
	v_cndmask_b32_e64 v17, v20, v17, s[4:5]
	v_cmp_lt_f32_e64 s[4:5], 0, v23
	v_add_f32_e32 v7, 1.0, v7
	v_rcp_f32_e32 v6, v6
	v_cndmask_b32_e64 v0, v0, v1, s[4:5]
	v_cmp_lt_f32_e64 s[4:5], 0, v32
	v_rcp_f32_e32 v7, v7
	v_lshl_add_u64 v[2:3], s[46:47], 0, v[2:3]
	v_cndmask_b32_e64 v1, v17, v21, s[4:5]
	v_mul_f32_e32 v17, 0x37800000, v0
	v_mul_f32_e32 v19, 0x37800000, v1
	v_cndmask_b32_e32 v0, v0, v17, vcc
	v_cmp_class_f32_e32 vcc, v8, v113
	v_cndmask_b32_e64 v1, v1, v19, s[0:1]
	s_waitcnt vmcnt(3)
	v_lshlrev_b32_e32 v4, 16, v4
	v_cndmask_b32_e32 v0, v0, v8, vcc
	v_cmp_class_f32_e32 vcc, v18, v113
	v_mul_f32_e32 v0, v6, v0
	s_waitcnt vmcnt(2)
	v_lshlrev_b32_e32 v5, 16, v5
	v_cndmask_b32_e32 v1, v1, v18, vcc
	v_mul_f32_e32 v1, v7, v1
	v_mul_f32_e32 v0, v0, v4
	v_mul_f32_e32 v1, v1, v5
	v_cvt_pk_bf16_f32 v0, v0, s0
	v_cvt_pk_bf16_f32 v1, v1, s0
	global_store_short v[2:3], v0, off sc1
	global_store_short v[2:3], v1, off offset:64 sc1
	v_add_u32_e32 v0, v121, v80
	v_ashrrev_i32_e32 v1, 31, v0
	v_lshlrev_b64 v[2:3], 1, v[0:1]
	v_or_b32_e32 v0, 32, v0
	v_lshl_add_u64 v[4:5], s[8:9], 0, v[2:3]
	v_ashrrev_i32_e32 v1, 31, v0
	v_lshl_add_u64 v[0:1], v[0:1], 1, s[8:9]
	global_load_ushort v4, v[4:5], off
	s_nop 0
	global_load_ushort v5, v[0:1], off
	v_add_f32_e32 v0, v25, v117
	v_add_f32_e32 v1, v41, v118
	v_mul_f32_e32 v0, 0xbfb8aa3b, v0
	v_mul_f32_e32 v1, 0xbfb8aa3b, v1
	v_exp_f32_e32 v8, v0
	v_add_f32_e32 v7, v9, v68
	v_exp_f32_e32 v9, v1
	v_add_f32_e32 v6, v57, v119
	v_add_f32_e32 v8, 1.0, v8
	v_rcp_f32_e32 v8, v8
	v_add_f32_e32 v9, 1.0, v9
	v_rcp_f32_e32 v9, v9
	v_mul_f32_e32 v6, 0xbfb8aa3b, v6
	v_mul_f32_e32 v8, v8, v120
	v_add_f32_e32 v17, v8, v8
	v_mul_f32_e32 v9, v9, v16
	v_add_f32_e32 v18, v9, v9
	v_mul_f32_e32 v17, 0x3fb8aa3b, v17
	v_mul_f32_e32 v18, 0x3fb8aa3b, v18
	v_exp_f32_e32 v17, v17
	v_exp_f32_e32 v18, v18
	v_mul_f32_e32 v7, 0xbfb8aa3b, v7
	v_exp_f32_e32 v6, v6
	v_sub_f32_e32 v17, 1.0, v17
	v_sub_f32_e32 v18, 1.0, v18
	v_max_f32_e32 v17, 0, v17
	v_max_f32_e32 v18, 0, v18
	v_mul_f32_e32 v19, 0x4f800000, v17
	v_cmp_gt_f32_e32 vcc, s59, v17
	v_mul_f32_e32 v20, 0x4f800000, v18
	v_cmp_gt_f32_e64 s[0:1], s59, v18
	v_cndmask_b32_e32 v17, v17, v19, vcc
	v_sqrt_f32_e32 v19, v17
	v_cndmask_b32_e64 v18, v18, v20, s[0:1]
	v_sqrt_f32_e32 v20, v18
	v_exp_f32_e32 v7, v7
	v_add_u32_e32 v21, -1, v19
	v_fma_f32 v25, -v21, v19, v17
	v_add_u32_e32 v23, -1, v20
	v_add_u32_e32 v22, 1, v19
	v_fma_f32 v33, -v23, v20, v18
	v_cmp_ge_f32_e64 s[4:5], 0, v25
	v_add_u32_e32 v24, 1, v20
	v_fma_f32 v32, -v22, v19, v17
	v_cndmask_b32_e64 v19, v19, v21, s[4:5]
	v_cmp_ge_f32_e64 s[4:5], 0, v33
	v_fma_f32 v34, -v24, v20, v18
	v_add_f32_e32 v6, 1.0, v6
	v_cndmask_b32_e64 v20, v20, v23, s[4:5]
	v_cmp_lt_f32_e64 s[4:5], 0, v32
	v_add_f32_e32 v7, 1.0, v7
	v_rcp_f32_e32 v6, v6
	v_cndmask_b32_e64 v19, v19, v22, s[4:5]
	v_cmp_lt_f32_e64 s[4:5], 0, v34
	v_rcp_f32_e32 v7, v7
	v_mul_f32_e32 v21, 0x37800000, v19
	v_cndmask_b32_e64 v20, v20, v24, s[4:5]
	v_mul_f32_e32 v22, 0x37800000, v20
	v_cndmask_b32_e32 v19, v19, v21, vcc
	v_cmp_class_f32_e32 vcc, v17, v113
	v_cndmask_b32_e64 v20, v20, v22, s[0:1]
	v_lshl_add_u64 v[0:1], s[48:49], 0, v[2:3]
	v_cndmask_b32_e32 v17, v19, v17, vcc
	v_cmp_class_f32_e32 vcc, v18, v113
	v_mul_f32_e32 v6, v6, v17
	v_cvt_pk_bf16_f32 v8, v8, s0
	v_cndmask_b32_e32 v18, v20, v18, vcc
	v_mul_f32_e32 v7, v7, v18
	global_store_short v[0:1], v8, off sc1
	s_waitcnt vmcnt(2)
	v_lshlrev_b32_e32 v4, 16, v4
	s_waitcnt vmcnt(1)
	v_lshlrev_b32_e32 v5, 16, v5
	v_mul_f32_e32 v4, v6, v4
	v_mul_f32_e32 v5, v7, v5
	v_cvt_pk_bf16_f32 v6, v9, s0
	global_store_short v[0:1], v6, off offset:64 sc1
	v_cvt_pk_bf16_f32 v4, v4, s0
	v_lshl_add_u64 v[0:1], s[46:47], 0, v[2:3]
	v_cvt_pk_bf16_f32 v2, v5, s0
	global_store_short v[0:1], v4, off sc1
	global_store_short v[0:1], v2, off offset:64 sc1
	v_add_u32_e32 v0, v121, v81
	v_ashrrev_i32_e32 v1, 31, v0
	v_lshlrev_b64 v[2:3], 1, v[0:1]
	v_or_b32_e32 v0, 32, v0
	v_lshl_add_u64 v[4:5], s[8:9], 0, v[2:3]
	v_ashrrev_i32_e32 v1, 31, v0
	global_load_ushort v4, v[4:5], off
	v_lshl_add_u64 v[0:1], v[0:1], 1, s[8:9]
	global_load_ushort v0, v[0:1], off
	v_add_f32_e32 v1, v26, v117
	v_add_f32_e32 v5, v42, v118
	v_mul_f32_e32 v1, 0xbfb8aa3b, v1
	v_mul_f32_e32 v5, 0xbfb8aa3b, v5
	v_exp_f32_e32 v1, v1
	v_exp_f32_e32 v5, v5
	v_add_f32_e32 v7, v10, v68
	v_add_f32_e32 v6, v58, v119
	v_add_f32_e32 v1, 1.0, v1
	v_add_f32_e32 v5, 1.0, v5
	v_rcp_f32_e32 v1, v1
	v_rcp_f32_e32 v5, v5
	v_mul_f32_e32 v6, 0xbfb8aa3b, v6
	v_mul_f32_e32 v7, 0xbfb8aa3b, v7
	v_mul_f32_e32 v1, v1, v120
	v_mul_f32_e32 v5, v5, v16
	v_add_f32_e32 v8, v1, v1
	v_add_f32_e32 v9, v5, v5
	v_mul_f32_e32 v8, 0x3fb8aa3b, v8
	v_mul_f32_e32 v9, 0x3fb8aa3b, v9
	v_exp_f32_e32 v8, v8
	v_exp_f32_e32 v9, v9
	v_exp_f32_e32 v6, v6
	v_exp_f32_e32 v7, v7
	v_sub_f32_e32 v8, 1.0, v8
	v_sub_f32_e32 v9, 1.0, v9
	v_max_f32_e32 v8, 0, v8
	v_max_f32_e32 v9, 0, v9
	v_mul_f32_e32 v10, 0x4f800000, v8
	v_cmp_gt_f32_e32 vcc, s59, v8
	v_mul_f32_e32 v17, 0x4f800000, v9
	v_cmp_gt_f32_e64 s[0:1], s59, v9
	v_cndmask_b32_e32 v8, v8, v10, vcc
	v_sqrt_f32_e32 v10, v8
	v_cndmask_b32_e64 v9, v9, v17, s[0:1]
	v_sqrt_f32_e32 v17, v9
	v_add_f32_e32 v6, 1.0, v6
	v_add_u32_e32 v18, -1, v10
	v_fma_f32 v22, -v18, v10, v8
	v_add_u32_e32 v20, -1, v17
	v_add_u32_e32 v19, 1, v10
	v_fma_f32 v24, -v20, v17, v9
	v_cmp_ge_f32_e64 s[4:5], 0, v22
	v_add_u32_e32 v21, 1, v17
	v_fma_f32 v23, -v19, v10, v8
	v_cndmask_b32_e64 v10, v10, v18, s[4:5]
	v_cmp_ge_f32_e64 s[4:5], 0, v24
	v_fma_f32 v25, -v21, v17, v9
	v_add_f32_e32 v7, 1.0, v7
	v_cndmask_b32_e64 v17, v17, v20, s[4:5]
	v_cmp_lt_f32_e64 s[4:5], 0, v23
	v_rcp_f32_e32 v6, v6
	v_rcp_f32_e32 v7, v7
	v_cndmask_b32_e64 v10, v10, v19, s[4:5]
	v_cmp_lt_f32_e64 s[4:5], 0, v25
	v_mul_f32_e32 v18, 0x37800000, v10
	v_cndmask_b32_e32 v10, v10, v18, vcc
	v_cndmask_b32_e64 v17, v17, v21, s[4:5]
	v_mul_f32_e32 v19, 0x37800000, v17
	v_cmp_class_f32_e32 vcc, v8, v113
	v_cndmask_b32_e64 v17, v17, v19, s[0:1]
	v_cvt_pk_bf16_f32 v5, v5, s0
	v_cndmask_b32_e32 v8, v10, v8, vcc
	v_cmp_class_f32_e32 vcc, v9, v113
	v_mul_f32_e32 v6, v6, v8
	s_waitcnt vmcnt(1)
	v_lshlrev_b32_e32 v4, 16, v4
	v_cndmask_b32_e32 v9, v17, v9, vcc
	v_mul_f32_e32 v4, v6, v4
	v_mul_f32_e32 v6, v7, v9
	s_waitcnt vmcnt(0)
	v_lshlrev_b32_e32 v0, 16, v0
	v_mul_f32_e32 v6, v6, v0
	v_cvt_pk_bf16_f32 v7, v1, s0
	v_lshl_add_u64 v[0:1], s[48:49], 0, v[2:3]
	global_store_short v[0:1], v7, off sc1
	global_store_short v[0:1], v5, off offset:64 sc1
	v_cvt_pk_bf16_f32 v4, v4, s0
	v_lshl_add_u64 v[0:1], s[46:47], 0, v[2:3]
	v_cvt_pk_bf16_f32 v2, v6, s0
	global_store_short v[0:1], v4, off sc1
	global_store_short v[0:1], v2, off offset:64 sc1
	v_add_u32_e32 v0, v121, v82
	v_ashrrev_i32_e32 v1, 31, v0
	v_lshlrev_b64 v[2:3], 1, v[0:1]
	v_lshl_add_u64 v[4:5], s[8:9], 0, v[2:3]
	global_load_ushort v4, v[4:5], off
	v_or_b32_e32 v0, 32, v0
	v_ashrrev_i32_e32 v1, 31, v0
	v_lshl_add_u64 v[0:1], v[0:1], 1, s[8:9]
	global_load_ushort v0, v[0:1], off
	v_add_f32_e32 v1, v27, v117
	v_add_f32_e32 v5, v43, v118
	v_mul_f32_e32 v1, 0xbfb8aa3b, v1
	v_mul_f32_e32 v5, 0xbfb8aa3b, v5
	v_exp_f32_e32 v1, v1
	v_exp_f32_e32 v5, v5
	v_add_f32_e32 v7, v11, v68
	v_add_f32_e32 v6, v59, v119
	v_add_f32_e32 v1, 1.0, v1
	v_add_f32_e32 v5, 1.0, v5
	v_rcp_f32_e32 v1, v1
	v_rcp_f32_e32 v5, v5
	v_mul_f32_e32 v6, 0xbfb8aa3b, v6
	v_exp_f32_e32 v6, v6
	v_mul_f32_e32 v1, v1, v120
	v_mul_f32_e32 v5, v5, v16
	v_add_f32_e32 v8, v1, v1
	v_add_f32_e32 v9, v5, v5
	v_mul_f32_e32 v8, 0x3fb8aa3b, v8
	v_mul_f32_e32 v9, 0x3fb8aa3b, v9
	v_exp_f32_e32 v8, v8
	v_exp_f32_e32 v9, v9
	v_add_f32_e32 v6, 1.0, v6
	v_mul_f32_e32 v7, 0xbfb8aa3b, v7
	v_sub_f32_e32 v8, 1.0, v8
	v_sub_f32_e32 v9, 1.0, v9
	v_max_f32_e32 v8, 0, v8
	v_max_f32_e32 v9, 0, v9
	v_mul_f32_e32 v10, 0x4f800000, v8
	v_cmp_gt_f32_e32 vcc, s59, v8
	v_mul_f32_e32 v11, 0x4f800000, v9
	v_cmp_gt_f32_e64 s[0:1], s59, v9
	v_cndmask_b32_e32 v8, v8, v10, vcc
	v_sqrt_f32_e32 v10, v8
	v_cndmask_b32_e64 v9, v9, v11, s[0:1]
	v_sqrt_f32_e32 v11, v9
	v_rcp_f32_e32 v6, v6
	v_add_u32_e32 v17, -1, v10
	v_fma_f32 v21, -v17, v10, v8
	v_add_u32_e32 v19, -1, v11
	v_add_u32_e32 v18, 1, v10
	v_fma_f32 v23, -v19, v11, v9
	v_cmp_ge_f32_e64 s[4:5], 0, v21
	v_add_u32_e32 v20, 1, v11
	v_fma_f32 v22, -v18, v10, v8
	v_cndmask_b32_e64 v10, v10, v17, s[4:5]
	v_cmp_ge_f32_e64 s[4:5], 0, v23
	v_fma_f32 v24, -v20, v11, v9
	v_exp_f32_e32 v7, v7
	v_cndmask_b32_e64 v11, v11, v19, s[4:5]
	v_cmp_lt_f32_e64 s[4:5], 0, v22
	v_cvt_pk_bf16_f32 v5, v5, s0
	s_waitcnt vmcnt(1)
	v_lshlrev_b32_e32 v4, 16, v4
	v_cndmask_b32_e64 v10, v10, v18, s[4:5]
	v_mul_f32_e32 v17, 0x37800000, v10
	v_cndmask_b32_e32 v10, v10, v17, vcc
	v_cmp_class_f32_e32 vcc, v8, v113
	v_cmp_lt_f32_e64 s[4:5], 0, v24
	s_waitcnt vmcnt(0)
	v_lshlrev_b32_e32 v0, 16, v0
	v_cndmask_b32_e32 v8, v10, v8, vcc
	v_mul_f32_e32 v6, v6, v8
	v_mul_f32_e32 v4, v6, v4
	v_add_f32_e32 v6, 1.0, v7
	v_cndmask_b32_e64 v11, v11, v20, s[4:5]
	v_rcp_f32_e32 v6, v6
	v_mul_f32_e32 v18, 0x37800000, v11
	v_cndmask_b32_e64 v7, v11, v18, s[0:1]
	v_cmp_class_f32_e32 vcc, v9, v113
	v_cvt_pk_bf16_f32 v4, v4, s0
	s_nop 0
	v_cndmask_b32_e32 v7, v7, v9, vcc
	v_mul_f32_e32 v6, v6, v7
	v_mul_f32_e32 v6, v6, v0
	v_cvt_pk_bf16_f32 v7, v1, s0
	v_lshl_add_u64 v[0:1], s[48:49], 0, v[2:3]
	global_store_short v[0:1], v7, off sc1
	global_store_short v[0:1], v5, off offset:64 sc1
	v_lshl_add_u64 v[0:1], s[46:47], 0, v[2:3]
	v_cvt_pk_bf16_f32 v2, v6, s0
	global_store_short v[0:1], v4, off sc1
	global_store_short v[0:1], v2, off offset:64 sc1
	v_add_u32_e32 v0, v121, v83
	v_ashrrev_i32_e32 v1, 31, v0
	v_lshlrev_b64 v[2:3], 1, v[0:1]
	v_or_b32_e32 v0, 32, v0
	v_lshl_add_u64 v[4:5], s[8:9], 0, v[2:3]
	v_ashrrev_i32_e32 v1, 31, v0
	v_lshl_add_u64 v[0:1], v[0:1], 1, s[8:9]
	global_load_ushort v4, v[4:5], off
	s_nop 0
	global_load_ushort v5, v[0:1], off
	v_add_f32_e32 v0, v28, v117
	v_add_f32_e32 v1, v44, v118
	v_mul_f32_e32 v0, 0xbfb8aa3b, v0
	v_mul_f32_e32 v1, 0xbfb8aa3b, v1
	v_exp_f32_e32 v8, v0
	v_exp_f32_e32 v9, v1
	v_lshl_add_u64 v[0:1], s[48:49], 0, v[2:3]
	v_add_f32_e32 v7, v12, v68
	v_add_f32_e32 v8, 1.0, v8
	v_add_f32_e32 v9, 1.0, v9
	v_rcp_f32_e32 v8, v8
	v_rcp_f32_e32 v9, v9
	v_add_f32_e32 v6, v60, v119
	v_mul_f32_e32 v6, 0xbfb8aa3b, v6
	v_mul_f32_e32 v8, v8, v120
	v_mul_f32_e32 v9, v9, v16
	v_add_f32_e32 v10, v8, v8
	v_add_f32_e32 v11, v9, v9
	v_mul_f32_e32 v10, 0x3fb8aa3b, v10
	v_mul_f32_e32 v11, 0x3fb8aa3b, v11
	v_exp_f32_e32 v10, v10
	v_exp_f32_e32 v11, v11
	v_cvt_pk_bf16_f32 v8, v8, s0
	global_store_short v[0:1], v8, off sc1
	v_sub_f32_e32 v8, 1.0, v10
	v_sub_f32_e32 v10, 1.0, v11
	v_max_f32_e32 v8, 0, v8
	v_max_f32_e32 v10, 0, v10
	v_mul_f32_e32 v11, 0x4f800000, v8
	v_cmp_gt_f32_e32 vcc, s59, v8
	v_cvt_pk_bf16_f32 v9, v9, s0
	v_mul_f32_e32 v12, 0x4f800000, v10
	v_cndmask_b32_e32 v8, v8, v11, vcc
	v_cmp_gt_f32_e64 s[0:1], s59, v10
	v_sqrt_f32_e32 v11, v8
	v_mul_f32_e32 v7, 0xbfb8aa3b, v7
	v_cndmask_b32_e64 v10, v10, v12, s[0:1]
	v_sqrt_f32_e32 v12, v10
	v_exp_f32_e32 v6, v6
	global_store_short v[0:1], v9, off offset:64 sc1
	v_add_u32_e32 v0, -1, v11
	v_exp_f32_e32 v7, v7
	v_add_u32_e32 v9, -1, v12
	v_fma_f32 v18, -v0, v11, v8
	v_add_u32_e32 v1, 1, v11
	v_fma_f32 v20, -v9, v12, v10
	v_cmp_ge_f32_e64 s[4:5], 0, v18
	v_add_u32_e32 v17, 1, v12
	v_fma_f32 v19, -v1, v11, v8
	v_cndmask_b32_e64 v0, v11, v0, s[4:5]
	v_cmp_ge_f32_e64 s[4:5], 0, v20
	v_add_f32_e32 v6, 1.0, v6
	v_fma_f32 v21, -v17, v12, v10
	v_cndmask_b32_e64 v9, v12, v9, s[4:5]
	v_cmp_lt_f32_e64 s[4:5], 0, v19
	v_add_f32_e32 v7, 1.0, v7
	v_rcp_f32_e32 v6, v6
	v_cndmask_b32_e64 v0, v0, v1, s[4:5]
	v_cmp_lt_f32_e64 s[4:5], 0, v21
	v_rcp_f32_e32 v7, v7
	v_lshl_add_u64 v[2:3], s[46:47], 0, v[2:3]
	v_cndmask_b32_e64 v1, v9, v17, s[4:5]
	v_mul_f32_e32 v9, 0x37800000, v0
	v_mul_f32_e32 v11, 0x37800000, v1
	v_cndmask_b32_e32 v0, v0, v9, vcc
	v_cmp_class_f32_e32 vcc, v8, v113
	v_cndmask_b32_e64 v1, v1, v11, s[0:1]
	s_waitcnt vmcnt(3)
	v_lshlrev_b32_e32 v4, 16, v4
	v_cndmask_b32_e32 v0, v0, v8, vcc
	v_cmp_class_f32_e32 vcc, v10, v113
	v_mul_f32_e32 v0, v6, v0
	s_waitcnt vmcnt(2)
	v_lshlrev_b32_e32 v5, 16, v5
	v_cndmask_b32_e32 v1, v1, v10, vcc
	v_mul_f32_e32 v1, v7, v1
	v_mul_f32_e32 v0, v0, v4
	v_mul_f32_e32 v1, v1, v5
	v_cvt_pk_bf16_f32 v0, v0, s0
	v_cvt_pk_bf16_f32 v1, v1, s0
	global_store_short v[2:3], v0, off sc1
	global_store_short v[2:3], v1, off offset:64 sc1
	v_add_u32_e32 v0, v121, v84
	v_ashrrev_i32_e32 v1, 31, v0
	v_lshlrev_b64 v[2:3], 1, v[0:1]
	v_or_b32_e32 v0, 32, v0
	v_lshl_add_u64 v[4:5], s[8:9], 0, v[2:3]
	v_ashrrev_i32_e32 v1, 31, v0
	v_lshl_add_u64 v[0:1], v[0:1], 1, s[8:9]
	global_load_ushort v4, v[4:5], off
	s_nop 0
	global_load_ushort v5, v[0:1], off
	v_add_f32_e32 v0, v29, v117
	v_add_f32_e32 v1, v45, v118
	v_mul_f32_e32 v0, 0xbfb8aa3b, v0
	v_mul_f32_e32 v1, 0xbfb8aa3b, v1
	v_exp_f32_e32 v8, v0
	v_exp_f32_e32 v9, v1
	v_add_f32_e32 v7, v13, v68
	v_add_f32_e32 v6, v61, v119
	v_add_f32_e32 v8, 1.0, v8
	v_add_f32_e32 v9, 1.0, v9
	v_rcp_f32_e32 v8, v8
	v_rcp_f32_e32 v9, v9
	v_mul_f32_e32 v6, 0xbfb8aa3b, v6
	v_mul_f32_e32 v7, 0xbfb8aa3b, v7
	v_mul_f32_e32 v8, v8, v120
	v_mul_f32_e32 v9, v9, v16
	v_add_f32_e32 v10, v8, v8
	v_add_f32_e32 v11, v9, v9
	v_mul_f32_e32 v10, 0x3fb8aa3b, v10
	v_mul_f32_e32 v11, 0x3fb8aa3b, v11
	v_exp_f32_e32 v10, v10
	v_exp_f32_e32 v11, v11
	v_exp_f32_e32 v6, v6
	v_exp_f32_e32 v7, v7
	v_sub_f32_e32 v10, 1.0, v10
	v_sub_f32_e32 v11, 1.0, v11
	v_max_f32_e32 v10, 0, v10
	v_max_f32_e32 v11, 0, v11
	v_mul_f32_e32 v12, 0x4f800000, v10
	v_cmp_gt_f32_e32 vcc, s59, v10
	v_mul_f32_e32 v13, 0x4f800000, v11
	v_cmp_gt_f32_e64 s[0:1], s59, v11
	v_cndmask_b32_e32 v10, v10, v12, vcc
	v_sqrt_f32_e32 v12, v10
	v_cndmask_b32_e64 v11, v11, v13, s[0:1]
	v_sqrt_f32_e32 v13, v11
	v_add_f32_e32 v6, 1.0, v6
	v_add_u32_e32 v17, -1, v12
	v_fma_f32 v21, -v17, v12, v10
	v_add_u32_e32 v19, -1, v13
	v_add_u32_e32 v18, 1, v12
	v_fma_f32 v23, -v19, v13, v11
	v_cmp_ge_f32_e64 s[4:5], 0, v21
	v_add_u32_e32 v20, 1, v13
	v_fma_f32 v22, -v18, v12, v10
	v_cndmask_b32_e64 v12, v12, v17, s[4:5]
	v_cmp_ge_f32_e64 s[4:5], 0, v23
	v_fma_f32 v24, -v20, v13, v11
	v_add_f32_e32 v7, 1.0, v7
	v_cndmask_b32_e64 v13, v13, v19, s[4:5]
	v_cmp_lt_f32_e64 s[4:5], 0, v22
	v_rcp_f32_e32 v6, v6
	v_rcp_f32_e32 v7, v7
	v_cndmask_b32_e64 v12, v12, v18, s[4:5]
	v_cmp_lt_f32_e64 s[4:5], 0, v24
	v_mul_f32_e32 v17, 0x37800000, v12
	v_cndmask_b32_e32 v12, v12, v17, vcc
	v_cndmask_b32_e64 v13, v13, v20, s[4:5]
	v_mul_f32_e32 v18, 0x37800000, v13
	v_cmp_class_f32_e32 vcc, v10, v113
	v_cndmask_b32_e64 v13, v13, v18, s[0:1]
	v_lshl_add_u64 v[0:1], s[48:49], 0, v[2:3]
	v_cndmask_b32_e32 v10, v12, v10, vcc
	v_cmp_class_f32_e32 vcc, v11, v113
	v_mul_f32_e32 v6, v6, v10
	v_cvt_pk_bf16_f32 v8, v8, s0
	v_cndmask_b32_e32 v11, v13, v11, vcc
	v_mul_f32_e32 v7, v7, v11
	global_store_short v[0:1], v8, off sc1
	s_waitcnt vmcnt(2)
	v_lshlrev_b32_e32 v4, 16, v4
	s_waitcnt vmcnt(1)
	v_lshlrev_b32_e32 v5, 16, v5
	v_mul_f32_e32 v4, v6, v4
	v_mul_f32_e32 v5, v7, v5
	v_cvt_pk_bf16_f32 v6, v9, s0
	global_store_short v[0:1], v6, off offset:64 sc1
	v_cvt_pk_bf16_f32 v4, v4, s0
	v_lshl_add_u64 v[0:1], s[46:47], 0, v[2:3]
	v_cvt_pk_bf16_f32 v2, v5, s0
	global_store_short v[0:1], v4, off sc1
	global_store_short v[0:1], v2, off offset:64 sc1
	v_add_u32_e32 v0, v121, v85
	v_ashrrev_i32_e32 v1, 31, v0
	v_lshlrev_b64 v[2:3], 1, v[0:1]
	v_or_b32_e32 v0, 32, v0
	v_lshl_add_u64 v[4:5], s[8:9], 0, v[2:3]
	v_ashrrev_i32_e32 v1, 31, v0
	global_load_ushort v4, v[4:5], off
	v_lshl_add_u64 v[0:1], v[0:1], 1, s[8:9]
	global_load_ushort v0, v[0:1], off
	v_add_f32_e32 v1, v30, v117
	v_add_f32_e32 v5, v46, v118
	v_mul_f32_e32 v1, 0xbfb8aa3b, v1
	v_mul_f32_e32 v5, 0xbfb8aa3b, v5
	v_exp_f32_e32 v1, v1
	v_exp_f32_e32 v5, v5
	v_add_f32_e32 v6, v62, v119
	v_add_f32_e32 v7, v14, v68
	v_add_f32_e32 v1, 1.0, v1
	v_add_f32_e32 v5, 1.0, v5
	v_rcp_f32_e32 v1, v1
	v_rcp_f32_e32 v5, v5
	v_mul_f32_e32 v6, 0xbfb8aa3b, v6
	v_mul_f32_e32 v7, 0xbfb8aa3b, v7
	v_mul_f32_e32 v1, v1, v120
	v_mul_f32_e32 v5, v5, v16
	v_add_f32_e32 v8, v1, v1
	v_add_f32_e32 v9, v5, v5
	v_mul_f32_e32 v8, 0x3fb8aa3b, v8
	v_mul_f32_e32 v9, 0x3fb8aa3b, v9
	v_exp_f32_e32 v8, v8
	v_exp_f32_e32 v9, v9
	v_exp_f32_e32 v6, v6
	v_exp_f32_e32 v7, v7
	v_sub_f32_e32 v8, 1.0, v8
	v_sub_f32_e32 v9, 1.0, v9
	v_max_f32_e32 v8, 0, v8
	v_max_f32_e32 v9, 0, v9
	v_mul_f32_e32 v10, 0x4f800000, v8
	v_cmp_gt_f32_e32 vcc, s59, v8
	v_mul_f32_e32 v11, 0x4f800000, v9
	v_cmp_gt_f32_e64 s[0:1], s59, v9
	v_cndmask_b32_e32 v8, v8, v10, vcc
	v_sqrt_f32_e32 v10, v8
	v_cndmask_b32_e64 v9, v9, v11, s[0:1]
	v_sqrt_f32_e32 v11, v9
	v_add_f32_e32 v6, 1.0, v6
	v_add_u32_e32 v12, -1, v10
	v_fma_f32 v18, -v12, v10, v8
	v_add_u32_e32 v14, -1, v11
	v_add_u32_e32 v13, 1, v10
	v_fma_f32 v20, -v14, v11, v9
	v_cmp_ge_f32_e64 s[4:5], 0, v18
	v_add_u32_e32 v17, 1, v11
	v_fma_f32 v19, -v13, v10, v8
	v_cndmask_b32_e64 v10, v10, v12, s[4:5]
	v_cmp_ge_f32_e64 s[4:5], 0, v20
	v_fma_f32 v21, -v17, v11, v9
	v_add_f32_e32 v7, 1.0, v7
	v_cndmask_b32_e64 v11, v11, v14, s[4:5]
	v_cmp_lt_f32_e64 s[4:5], 0, v19
	v_rcp_f32_e32 v6, v6
	v_rcp_f32_e32 v7, v7
	v_cndmask_b32_e64 v10, v10, v13, s[4:5]
	v_cmp_lt_f32_e64 s[4:5], 0, v21
	v_mul_f32_e32 v12, 0x37800000, v10
	v_cndmask_b32_e32 v10, v10, v12, vcc
	v_cndmask_b32_e64 v11, v11, v17, s[4:5]
	v_mul_f32_e32 v13, 0x37800000, v11
	v_cmp_class_f32_e32 vcc, v8, v113
	v_cndmask_b32_e64 v11, v11, v13, s[0:1]
	v_cvt_pk_bf16_f32 v5, v5, s0
	v_cndmask_b32_e32 v8, v10, v8, vcc
	v_cmp_class_f32_e32 vcc, v9, v113
	v_mul_f32_e32 v6, v6, v8
	s_waitcnt vmcnt(1)
	v_lshlrev_b32_e32 v4, 16, v4
	v_cndmask_b32_e32 v9, v11, v9, vcc
	v_mul_f32_e32 v4, v6, v4
	v_mul_f32_e32 v6, v7, v9
	s_waitcnt vmcnt(0)
	v_lshlrev_b32_e32 v0, 16, v0
	v_mul_f32_e32 v6, v6, v0
	v_cvt_pk_bf16_f32 v7, v1, s0
	v_lshl_add_u64 v[0:1], s[48:49], 0, v[2:3]
	global_store_short v[0:1], v7, off sc1
	global_store_short v[0:1], v5, off offset:64 sc1
	v_cvt_pk_bf16_f32 v4, v4, s0
	v_lshl_add_u64 v[0:1], s[46:47], 0, v[2:3]
	v_cvt_pk_bf16_f32 v2, v6, s0
	global_store_short v[0:1], v4, off sc1
	global_store_short v[0:1], v2, off offset:64 sc1
	v_add_u32_e32 v0, v121, v86
	v_ashrrev_i32_e32 v1, 31, v0
	v_lshlrev_b64 v[2:3], 1, v[0:1]
	v_lshl_add_u64 v[4:5], s[8:9], 0, v[2:3]
	global_load_ushort v4, v[4:5], off
	v_or_b32_e32 v0, 32, v0
	v_ashrrev_i32_e32 v1, 31, v0
	v_lshl_add_u64 v[0:1], v[0:1], 1, s[8:9]
	global_load_ushort v0, v[0:1], off
	v_add_f32_e32 v1, v31, v117
	v_add_f32_e32 v5, v47, v118
	v_mul_f32_e32 v1, 0xbfb8aa3b, v1
	v_mul_f32_e32 v5, 0xbfb8aa3b, v5
	v_exp_f32_e32 v1, v1
	v_exp_f32_e32 v5, v5
	v_add_f32_e32 v6, v63, v119
	v_mul_f32_e32 v6, 0xbfb8aa3b, v6
	v_add_f32_e32 v1, 1.0, v1
	v_add_f32_e32 v5, 1.0, v5
	v_rcp_f32_e32 v1, v1
	v_rcp_f32_e32 v5, v5
	v_exp_f32_e32 v6, v6
	v_add_f32_e32 v7, v15, v68
	v_mul_f32_e32 v1, v1, v120
	v_mul_f32_e32 v5, v5, v16
	v_add_f32_e32 v8, v1, v1
	v_add_f32_e32 v9, v5, v5
	v_mul_f32_e32 v8, 0x3fb8aa3b, v8
	v_mul_f32_e32 v9, 0x3fb8aa3b, v9
	v_exp_f32_e32 v8, v8
	v_exp_f32_e32 v9, v9
	v_add_f32_e32 v6, 1.0, v6
	v_mul_f32_e32 v7, 0xbfb8aa3b, v7
	v_sub_f32_e32 v8, 1.0, v8
	v_sub_f32_e32 v9, 1.0, v9
	v_max_f32_e32 v8, 0, v8
	v_max_f32_e32 v9, 0, v9
	v_mul_f32_e32 v10, 0x4f800000, v8
	v_cmp_gt_f32_e32 vcc, s59, v8
	v_mul_f32_e32 v11, 0x4f800000, v9
	v_cmp_gt_f32_e64 s[0:1], s59, v9
	v_cndmask_b32_e32 v8, v8, v10, vcc
	v_sqrt_f32_e32 v10, v8
	v_cndmask_b32_e64 v9, v9, v11, s[0:1]
	v_sqrt_f32_e32 v11, v9
	v_rcp_f32_e32 v6, v6
	v_add_u32_e32 v12, -1, v10
	v_fma_f32 v16, -v12, v10, v8
	v_add_u32_e32 v14, -1, v11
	v_add_u32_e32 v13, 1, v10
	v_fma_f32 v18, -v14, v11, v9
	v_cmp_ge_f32_e64 s[4:5], 0, v16
	v_add_u32_e32 v15, 1, v11
	v_fma_f32 v17, -v13, v10, v8
	v_cndmask_b32_e64 v10, v10, v12, s[4:5]
	v_cmp_ge_f32_e64 s[4:5], 0, v18
	v_fma_f32 v19, -v15, v11, v9
	v_exp_f32_e32 v7, v7
	v_cndmask_b32_e64 v11, v11, v14, s[4:5]
	v_cmp_lt_f32_e64 s[4:5], 0, v17
	v_cvt_pk_bf16_f32 v5, v5, s0
	s_waitcnt vmcnt(1)
	v_lshlrev_b32_e32 v4, 16, v4
	v_cndmask_b32_e64 v10, v10, v13, s[4:5]
	v_mul_f32_e32 v12, 0x37800000, v10
	v_cndmask_b32_e32 v10, v10, v12, vcc
	v_cmp_class_f32_e32 vcc, v8, v113
	v_cmp_lt_f32_e64 s[4:5], 0, v19
	s_waitcnt vmcnt(0)
	v_lshlrev_b32_e32 v0, 16, v0
	v_cndmask_b32_e32 v8, v10, v8, vcc
	v_mul_f32_e32 v6, v6, v8
	v_mul_f32_e32 v4, v6, v4
	v_add_f32_e32 v6, 1.0, v7
	v_cndmask_b32_e64 v11, v11, v15, s[4:5]
	v_rcp_f32_e32 v6, v6
	v_mul_f32_e32 v13, 0x37800000, v11
	v_cndmask_b32_e64 v7, v11, v13, s[0:1]
	v_cmp_class_f32_e32 vcc, v9, v113
	v_cvt_pk_bf16_f32 v4, v4, s0
	s_nop 0
	v_cndmask_b32_e32 v7, v7, v9, vcc
	v_mul_f32_e32 v6, v6, v7
	v_mul_f32_e32 v6, v6, v0
	v_cvt_pk_bf16_f32 v7, v1, s0
	v_lshl_add_u64 v[0:1], s[48:49], 0, v[2:3]
	global_store_short v[0:1], v7, off sc1
	global_store_short v[0:1], v5, off offset:64 sc1
	v_lshl_add_u64 v[0:1], s[46:47], 0, v[2:3]
	v_cvt_pk_bf16_f32 v2, v6, s0
	global_store_short v[0:1], v4, off sc1
	global_store_short v[0:1], v2, off offset:64 sc1
	s_add_i32 s3, s3, s33
	s_cmpk_lt_i32 s3, 0x1000
	s_cbranch_scc1 .LBB0_1494
.LBB0_1495:
	s_cmp_gt_i32 s17, 22
	s_cselect_b64 s[4:5], -1, 0
	s_and_b64 s[0:1], s[6:7], s[4:5]
	s_andn2_b64 vcc, exec, s[0:1]
	s_cbranch_vccnz .LBB0_1507
	s_waitcnt vmcnt(0)
	v_or_b32_e32 v0, v201, v200
	s_movk_i32 s0, 0x3ff
	v_and_or_b32 v0, v0, s0, v199
	v_cmp_eq_u32_e32 vcc, 0, v0
	s_waitcnt lgkmcnt(0)
	s_barrier
	s_and_saveexec_b64 s[0:1], vcc
	s_cbranch_execz .LBB0_1506
	s_add_u32 s6, s14, 0x5be8c00
	s_addc_u32 s7, s15, 0
	s_lshl_b32 s3, s2, 1
	v_mov_b32_e32 v0, s3
	v_mov_b32_e32 v1, 0x9316
	global_store_short v0, v1, s[6:7] sc1
	s_cmp_lg_u32 s2, 0
	s_cbranch_scc1 .Lgbar_wait_21
	s_lshr_b32 s3, s33, 3
	s_bfm_b64 s[8:9], s3, 0
	s_cmpk_gt_u32 s33, 0x1ff
	s_cselect_b64 s[8:9], -1, s[8:9]
	s_mov_b64 exec, -1
	v_mbcnt_lo_u32_b32 v229, -1, 0
	v_mbcnt_hi_u32_b32 v229, -1, v229
	v_lshlrev_b32_e32 v229, 4, v229
	s_mov_b32 s10, 0x93169316
	s_mov_b64 exec, s[8:9]

.LBB0_1511:
	s_add_i32 s8, s19, 7
	s_and_b64 s[26:27], s[20:21], exec
	s_cselect_b32 s8, s25, s8
	s_add_i32 s28, s19, 6
	s_add_i32 s29, s25, 1
	s_lshl_b32 s8, s8, 11
	s_and_b64 s[26:27], s[20:21], exec
	v_lshl_add_u64 v[10:11], v[2:3], 0, s[8:9]
	v_lshl_add_u64 v[12:13], v[4:5], 0, s[8:9]
	s_cselect_b32 s8, s29, s28
	global_load_dword v14, v[10:11], off
	global_load_dword v15, v[12:13], off
	s_add_i32 s28, s19, 5
	s_add_i32 s29, s25, 2
	s_lshl_b32 s8, s8, 11
	v_lshl_add_u64 v[10:11], v[2:3], 0, s[8:9]
	s_and_b64 s[26:27], s[20:21], exec
	v_lshl_add_u64 v[12:13], v[4:5], 0, s[8:9]
	global_load_dword v16, v[10:11], off
	global_load_dword v17, v[12:13], off
	s_cselect_b32 s8, s29, s28
	s_add_i32 s28, s19, 4
	s_add_i32 s29, s25, 3
	s_lshl_b32 s8, s8, 11
	s_and_b64 s[26:27], s[20:21], exec
	v_lshl_add_u64 v[10:11], v[2:3], 0, s[8:9]
	v_lshl_add_u64 v[12:13], v[4:5], 0, s[8:9]
	s_cselect_b32 s8, s29, s28
	s_add_i32 s28, s19, 3
	s_add_i32 s29, s25, 4
	s_lshl_b32 s8, s8, 11
	global_load_dword v18, v[10:11], off
	global_load_dword v19, v[12:13], off
	v_lshl_add_u64 v[10:11], v[2:3], 0, s[8:9]
	s_and_b64 s[26:27], s[20:21], exec
	v_lshl_add_u64 v[12:13], v[4:5], 0, s[8:9]
	global_load_dword v20, v[10:11], off
	global_load_dword v21, v[12:13], off
	s_cselect_b32 s8, s29, s28
	s_add_i32 s28, s19, 2
	s_add_i32 s29, s25, 5
	s_lshl_b32 s8, s8, 11
	s_and_b64 s[26:27], s[20:21], exec
	v_lshl_add_u64 v[10:11], v[2:3], 0, s[8:9]
	v_lshl_add_u64 v[12:13], v[4:5], 0, s[8:9]
	s_cselect_b32 s8, s29, s28
	s_add_i32 s28, s19, 1
	s_add_i32 s29, s25, 6
	s_lshl_b32 s8, s8, 11
	global_load_dword v22, v[10:11], off
	global_load_dword v23, v[12:13], off
	v_lshl_add_u64 v[10:11], v[2:3], 0, s[8:9]
	s_and_b64 s[26:27], s[20:21], exec
	v_lshl_add_u64 v[12:13], v[4:5], 0, s[8:9]
	global_load_dword v24, v[10:11], off
	global_load_dword v25, v[12:13], off
	s_cselect_b32 s8, s29, s28
	s_add_i32 s28, s25, 7
	s_lshl_b32 s8, s8, 11
	s_and_b64 s[26:27], s[20:21], exec
	v_lshl_add_u64 v[10:11], v[2:3], 0, s[8:9]
	v_lshl_add_u64 v[12:13], v[4:5], 0, s[8:9]
	s_cselect_b32 s8, s28, s19
	s_lshl_b32 s8, s8, 11
	global_load_dword v26, v[10:11], off
	global_load_dword v27, v[12:13], off
	v_lshl_add_u64 v[10:11], v[2:3], 0, s[8:9]
	v_lshl_add_u64 v[12:13], v[4:5], 0, s[8:9]
	global_load_dword v28, v[10:11], off
	global_load_dword v29, v[12:13], off
	s_add_i32 s19, s19, -8
	s_add_i32 s25, s25, 8
	s_cmp_eq_u32 s25, 64
	s_waitcnt vmcnt(15)
	v_lshlrev_b32_e32 v10, 16, v14
	v_and_b32_e32 v11, 0xffff0000, v14
	s_waitcnt vmcnt(14)
	v_lshlrev_b32_e32 v12, 16, v15
	v_and_b32_e32 v13, 0xffff0000, v15
	v_mul_f32_e32 v14, 0x3fb8aa3b, v10
	v_mul_f32_e32 v15, 0x3fb8aa3b, v11
	v_pk_add_f32 v[8:9], v[8:9], v[10:11]
	v_exp_f32_e32 v10, v14
	v_exp_f32_e32 v11, v15
	s_waitcnt vmcnt(13)
	v_lshlrev_b32_e32 v14, 16, v16
	v_and_b32_e32 v15, 0xffff0000, v16
	v_mul_f32_e32 v30, 0x3fb8aa3b, v14
	v_mul_f32_e32 v31, 0x3fb8aa3b, v15
	v_pk_add_f32 v[8:9], v[8:9], v[14:15]
	v_exp_f32_e32 v14, v30
	v_exp_f32_e32 v15, v31
	s_waitcnt vmcnt(12)
	v_lshlrev_b32_e32 v16, 16, v17
	v_and_b32_e32 v17, 0xffff0000, v17
	v_pk_fma_f32 v[6:7], v[6:7], v[10:11], v[12:13]
	s_waitcnt vmcnt(11)
	v_lshlrev_b32_e32 v10, 16, v18
	v_and_b32_e32 v11, 0xffff0000, v18
	s_waitcnt vmcnt(10)
	v_lshlrev_b32_e32 v12, 16, v19
	v_and_b32_e32 v13, 0xffff0000, v19
	v_mul_f32_e32 v18, 0x3fb8aa3b, v10
	v_mul_f32_e32 v19, 0x3fb8aa3b, v11
	v_pk_fma_f32 v[6:7], v[6:7], v[14:15], v[16:17]
	s_waitcnt vmcnt(9)
	v_lshlrev_b32_e32 v14, 16, v20
	v_and_b32_e32 v15, 0xffff0000, v20
	v_pk_add_f32 v[8:9], v[8:9], v[10:11]
	v_exp_f32_e32 v10, v18
	v_exp_f32_e32 v11, v19
	v_mul_f32_e32 v18, 0x3fb8aa3b, v14
	v_mul_f32_e32 v19, 0x3fb8aa3b, v15
	v_pk_add_f32 v[8:9], v[8:9], v[14:15]
	v_exp_f32_e32 v14, v18
	v_exp_f32_e32 v15, v19
	s_waitcnt vmcnt(8)
	v_lshlrev_b32_e32 v16, 16, v21
	v_and_b32_e32 v17, 0xffff0000, v21
	v_pk_fma_f32 v[6:7], v[6:7], v[10:11], v[12:13]
	s_waitcnt vmcnt(7)
	v_lshlrev_b32_e32 v10, 16, v22
	v_and_b32_e32 v11, 0xffff0000, v22
	v_mul_f32_e32 v18, 0x3fb8aa3b, v10
	v_mul_f32_e32 v19, 0x3fb8aa3b, v11
	v_pk_fma_f32 v[6:7], v[6:7], v[14:15], v[16:17]
	s_waitcnt vmcnt(5)
	v_lshlrev_b32_e32 v14, 16, v24
	v_and_b32_e32 v15, 0xffff0000, v24
	v_pk_add_f32 v[8:9], v[8:9], v[10:11]
	v_exp_f32_e32 v10, v18
	v_exp_f32_e32 v11, v19
	v_mul_f32_e32 v18, 0x3fb8aa3b, v14
	v_mul_f32_e32 v19, 0x3fb8aa3b, v15
	v_pk_add_f32 v[8:9], v[8:9], v[14:15]
	v_exp_f32_e32 v14, v18
	v_exp_f32_e32 v15, v19
	v_lshlrev_b32_e32 v12, 16, v23
	v_and_b32_e32 v13, 0xffff0000, v23
	s_waitcnt vmcnt(4)
	v_lshlrev_b32_e32 v16, 16, v25
	v_and_b32_e32 v17, 0xffff0000, v25
	v_pk_fma_f32 v[6:7], v[6:7], v[10:11], v[12:13]
	s_waitcnt vmcnt(3)
	v_lshlrev_b32_e32 v10, 16, v26
	v_and_b32_e32 v11, 0xffff0000, v26
	v_mul_f32_e32 v18, 0x3fb8aa3b, v10
	v_mul_f32_e32 v19, 0x3fb8aa3b, v11
	v_pk_fma_f32 v[6:7], v[6:7], v[14:15], v[16:17]
	s_waitcnt vmcnt(1)
	v_lshlrev_b32_e32 v14, 16, v28
	v_and_b32_e32 v15, 0xffff0000, v28
	v_pk_add_f32 v[8:9], v[8:9], v[10:11]
	v_exp_f32_e32 v10, v18
	v_exp_f32_e32 v11, v19
	v_mul_f32_e32 v17, 0x3fb8aa3b, v14
	v_mul_f32_e32 v19, 0x3fb8aa3b, v15
	v_exp_f32_e32 v18, v17
	v_exp_f32_e32 v19, v19
	v_lshlrev_b32_e32 v12, 16, v27
	v_and_b32_e32 v13, 0xffff0000, v27
	s_waitcnt vmcnt(0)
	v_lshlrev_b32_e32 v16, 16, v29
	v_and_b32_e32 v17, 0xffff0000, v29
	v_pk_fma_f32 v[6:7], v[6:7], v[10:11], v[12:13]
	v_pk_add_f32 v[8:9], v[8:9], v[14:15]
	v_pk_fma_f32 v[6:7], v[6:7], v[18:19], v[16:17]
	s_cbranch_scc0 .LBB0_1511
	s_lshl_b32 s8, s18, 18
	s_lshl_b32 s18, s24, 10
	s_or_b32 s18, s18, s8
	s_ashr_i32 s19, s18, 31
	s_lshl_b64 s[18:19], s[18:19], 2
	v_mul_f32_e32 v2, 0x3fb8aa3b, v8
	v_mul_f32_e32 v3, 0x3fb8aa3b, v9
	s_add_u32 s20, s3, s18
	v_exp_f32_e32 v2, v2
	v_exp_f32_e32 v3, v3
	s_addc_u32 s21, s10, s19
	s_add_u32 s18, s11, s18
	s_addc_u32 s19, s22, s19
	s_add_i32 s23, s23, s33
	v_lshlrev_b32_e32 v0, 2, v0
	s_cmpk_gt_i32 s23, 0x3ff
	global_store_dwordx2 v0, v[2:3], s[20:21] sc1
	global_store_dwordx2 v0, v[6:7], s[18:19] sc1
	s_cbranch_scc0 .LBB0_1510
.LBB0_1513:
	s_cmp_gt_i32 s17, 23
	s_cselect_b64 s[6:7], -1, 0
	s_and_b64 s[0:1], s[0:1], s[6:7]
	s_andn2_b64 vcc, exec, s[0:1]
	s_cbranch_vccnz .LBB0_1525
	s_waitcnt vmcnt(0)
	v_or_b32_e32 v0, v201, v200
	s_movk_i32 s0, 0x3ff
	v_and_or_b32 v0, v0, s0, v199
	v_cmp_eq_u32_e32 vcc, 0, v0
	s_waitcnt lgkmcnt(0)
	s_barrier
	s_and_saveexec_b64 s[0:1], vcc
	s_cbranch_execz .LBB0_1524
	s_add_u32 s4, s14, 0x5be8c00
	s_addc_u32 s5, s15, 0
	s_lshl_b32 s3, s2, 1
	v_mov_b32_e32 v0, s3
	v_mov_b32_e32 v1, 0x9317
	global_store_short v0, v1, s[4:5] sc1
	s_cmp_lg_u32 s2, 0
	s_cbranch_scc1 .Lgbar_wait_22
	s_lshr_b32 s3, s33, 3
	s_bfm_b64 s[8:9], s3, 0
	s_cmpk_gt_u32 s33, 0x1ff
	s_cselect_b64 s[8:9], -1, s[8:9]
	s_mov_b64 exec, -1
	v_mbcnt_lo_u32_b32 v229, -1, 0
	v_mbcnt_hi_u32_b32 v229, -1, v229
	v_lshlrev_b32_e32 v229, 4, v229
	s_mov_b32 s10, 0x93179317
	s_mov_b64 exec, s[8:9]

.LBB0_1542:
	v_lshl_add_u64 v[14:15], v[10:11], 0, s[24:25]
	v_add_co_u32_e64 v18, s[0:1], s28, v14
	v_add_co_u32_e32 v16, vcc, 0xff9f000, v14
	s_nop 0
	v_addc_co_u32_e64 v19, s[0:1], 0, v15, s[0:1]
	v_add_co_u32_e64 v20, s[0:1], s30, v14
	v_addc_co_u32_e32 v17, vcc, 0, v15, vcc
	s_nop 0
	v_addc_co_u32_e64 v21, s[0:1], 0, v15, s[0:1]
	v_add_co_u32_e64 v22, s[0:1], s29, v14
	s_add_u32 s24, s24, 0x4000
	s_nop 0
	v_addc_co_u32_e64 v23, s[0:1], 0, v15, s[0:1]
	v_add_co_u32_e64 v24, s[0:1], s31, v14
	s_addc_u32 s25, s25, 0
	s_nop 0
	v_addc_co_u32_e64 v25, s[0:1], 0, v15, s[0:1]
	v_add_co_u32_e64 v26, s[0:1], s34, v14
	s_cmp_eq_u32 s24, 0x20000
	s_nop 0
	v_addc_co_u32_e64 v27, s[0:1], 0, v15, s[0:1]
	v_add_co_u32_e64 v28, s[0:1], s35, v14
	v_add_co_u32_e32 v14, vcc, 0x13f9f000, v14
	s_nop 0
	v_addc_co_u32_e64 v29, s[0:1], 0, v15, s[0:1]
	global_load_dword v3, v[20:21], off offset:-4096
	global_load_dword v30, v[24:25], off offset:-4096
	global_load_dword v31, v[20:21], off
	global_load_dword v32, v[24:25], off
	global_load_dword v33, v[24:25], off offset:2048
	global_load_dword v34, v[20:21], off offset:2048
	global_load_dword v35, v[28:29], off
	v_addc_co_u32_e32 v15, vcc, 0, v15, vcc
	global_load_dword v24, v[16:17], off
	global_load_dword v25, v[14:15], off
	global_load_dword v36, v[14:15], off offset:2048
	global_load_dword v37, v[18:19], off offset:2048
	global_load_dword v38, v[22:23], off offset:2048
	global_load_dword v39, v[26:27], off
	global_load_dword v40, v[26:27], off offset:2048
	global_load_dword v41, v[16:17], off offset:2048
	global_load_dword v42, v[28:29], off offset:2048
	s_waitcnt vmcnt(15)
	v_lshlrev_b32_e32 v26, 16, v3
	s_waitcnt vmcnt(14)
	v_lshlrev_b32_e32 v14, 16, v30
	v_and_b32_e32 v3, 0xffff0000, v3
	v_and_b32_e32 v15, 0xffff0000, v30
	s_waitcnt vmcnt(13)
	v_lshlrev_b32_e32 v27, 16, v31
	s_waitcnt vmcnt(12)
	v_lshlrev_b32_e32 v16, 16, v32
	v_and_b32_e32 v28, 0xffff0000, v31
	v_and_b32_e32 v17, 0xffff0000, v32
	s_waitcnt vmcnt(10)
	v_and_b32_e32 v30, 0xffff0000, v34
	s_waitcnt vmcnt(8)
	v_lshlrev_b32_e32 v31, 16, v24
	v_and_b32_e32 v32, 0xffff0000, v24
	v_lshlrev_b32_e32 v29, 16, v34
	v_lshlrev_b32_e32 v18, 16, v33
	v_and_b32_e32 v19, 0xffff0000, v33
	v_lshlrev_b32_e32 v20, 16, v35
	v_and_b32_e32 v21, 0xffff0000, v35
	v_mul_f32_e32 v33, 0x3fb8aa3b, v26
	v_mul_f32_e32 v3, 0x3fb8aa3b, v3
	v_mul_f32_e32 v35, 0x3fb8aa3b, v28
	v_mul_f32_e32 v43, 0x3fb8aa3b, v30
	v_mul_f32_e32 v44, 0x3fb8aa3b, v31
	v_mul_f32_e32 v45, 0x3fb8aa3b, v32
	s_waitcnt vmcnt(1)
	v_lshlrev_b32_e32 v46, 16, v41
	v_and_b32_e32 v41, 0xffff0000, v41
	s_waitcnt vmcnt(0)
	v_lshlrev_b32_e32 v22, 16, v42
	v_and_b32_e32 v23, 0xffff0000, v42
	v_mul_f32_e32 v34, 0x3fb8aa3b, v27
	v_mul_f32_e32 v42, 0x3fb8aa3b, v29
	v_lshlrev_b32_e32 v26, 16, v36
	v_and_b32_e32 v27, 0xffff0000, v36
	v_exp_f32_e32 v28, v33
	v_exp_f32_e32 v29, v3
	v_lshlrev_b32_e32 v3, 16, v37
	v_lshlrev_b32_e32 v30, 16, v38
	v_and_b32_e32 v47, 0xffff0000, v37
	v_and_b32_e32 v31, 0xffff0000, v38
	v_exp_f32_e32 v33, v35
	v_exp_f32_e32 v35, v43
	v_lshlrev_b32_e32 v38, 16, v39
	v_and_b32_e32 v39, 0xffff0000, v39
	v_exp_f32_e32 v36, v44
	v_exp_f32_e32 v37, v45
	v_mul_f32_e32 v43, 0x3fb8aa3b, v46
	v_mul_f32_e32 v41, 0x3fb8aa3b, v41
	v_mul_f32_e32 v45, 0x3fb8aa3b, v38
	v_mul_f32_e32 v46, 0x3fb8aa3b, v39
	v_exp_f32_e32 v38, v43
	v_exp_f32_e32 v39, v41
	v_exp_f32_e32 v32, v34
	v_exp_f32_e32 v34, v42
	v_lshlrev_b32_e32 v42, 16, v40
	v_and_b32_e32 v40, 0xffff0000, v40
	v_mul_f32_e32 v3, 0x3fb8aa3b, v3
	v_mul_f32_e32 v44, 0x3fb8aa3b, v47
	v_lshlrev_b32_e32 v24, 16, v25
	v_and_b32_e32 v25, 0xffff0000, v25
	v_mul_f32_e32 v48, 0x3fb8aa3b, v40
	v_exp_f32_e32 v40, v3
	v_exp_f32_e32 v41, v44
	v_pk_fma_f32 v[6:7], v[6:7], v[36:37], v[24:25]
	v_mul_f32_e32 v47, 0x3fb8aa3b, v42
	v_cvt_pk_bf16_f32 v3, v6, v7
	v_pk_fma_f32 v[6:7], v[6:7], v[38:39], v[26:27]
	v_exp_f32_e32 v42, v45
	v_exp_f32_e32 v43, v46
	v_cvt_pk_bf16_f32 v24, v6, v7
	v_pk_fma_f32 v[6:7], v[6:7], v[28:29], v[14:15]
	v_exp_f32_e32 v44, v47
	v_exp_f32_e32 v45, v48
	ds_write2st64_b32 v1, v3, v24 offset1:4
	v_cvt_pk_bf16_f32 v3, v6, v7
	v_pk_fma_f32 v[6:7], v[6:7], v[40:41], v[30:31]
	s_nop 0
	v_cvt_pk_bf16_f32 v14, v6, v7
	v_pk_fma_f32 v[6:7], v[6:7], v[32:33], v[16:17]
	ds_write2st64_b32 v1, v3, v14 offset0:8 offset1:12
	v_cvt_pk_bf16_f32 v3, v6, v7
	v_pk_fma_f32 v[6:7], v[6:7], v[34:35], v[18:19]
	s_nop 0
	v_cvt_pk_bf16_f32 v14, v6, v7
	v_pk_fma_f32 v[6:7], v[6:7], v[42:43], v[20:21]
	ds_write2st64_b32 v1, v3, v14 offset0:16 offset1:20
	v_cvt_pk_bf16_f32 v3, v6, v7
	v_pk_fma_f32 v[6:7], v[6:7], v[44:45], v[22:23]
	s_nop 0
	v_cvt_pk_bf16_f32 v14, v6, v7
	ds_write2st64_b32 v1, v3, v14 offset0:24 offset1:28
	v_add_u32_e32 v1, 0x2000, v1
	s_cbranch_scc0 .LBB0_1542
	s_cmp_eq_u32 s46, s49
	s_cselect_b64 s[0:1], -1, 0
	s_and_b64 s[0:1], s[22:23], s[0:1]
	s_and_b64 vcc, exec, s[0:1]
	s_cbranch_vccz .LBB0_1545
	s_lshl_b32 s0, s47, 11
	s_ashr_i32 s1, s0, 31
	s_lshl_b64 s[0:1], s[0:1], 2
	s_add_u32 s0, s3, s0
	s_addc_u32 s1, s10, s1
	global_store_dwordx2 v2, v[6:7], s[0:1] sc1

.LBB0_1546:
	v_add_co_u32_e32 v10, vcc, 0x4003000, v6
	v_add_u32_e32 v32, s0, v12
	s_nop 0
	v_addc_co_u32_e32 v11, vcc, 0, v7, vcc
	v_add_co_u32_e32 v14, vcc, 0x8003000, v6
	s_addk_i32 s0, 0xe000
	s_nop 0
	v_addc_co_u32_e32 v15, vcc, 0, v7, vcc
	v_add_co_u32_e32 v8, vcc, s37, v6
	s_cmpk_eq_i32 s0, 0xe000
	s_nop 0
	v_addc_co_u32_e32 v9, vcc, 0, v7, vcc
	global_load_dword v1, v[10:11], off offset:2048
	global_load_dword v3, v[8:9], off offset:2048
	v_add_co_u32_e32 v16, vcc, s38, v6
	s_nop 1
	v_addc_co_u32_e32 v17, vcc, 0, v7, vcc
	global_load_dword v23, v[14:15], off offset:2048
	global_load_dword v28, v[16:17], off
	global_load_dword v29, v[8:9], off
	global_load_dword v30, v[14:15], off
	global_load_dword v26, v[10:11], off
	global_load_dword v31, v[16:17], off offset:2048
	v_add_co_u32_e32 v10, vcc, s39, v6
	s_waitcnt vmcnt(5)
	v_lshlrev_b32_e32 v22, 16, v23
	v_addc_co_u32_e32 v11, vcc, 0, v7, vcc
	global_load_dword v33, v[10:11], off offset:2048
	v_add_co_u32_e32 v14, vcc, s36, v6
	v_and_b32_e32 v23, 0xffff0000, v23
	s_nop 0
	v_addc_co_u32_e32 v15, vcc, 0, v7, vcc
	global_load_dword v34, v[14:15], off offset:2048
	v_add_co_u32_e32 v16, vcc, s40, v6
	s_nop 1
	v_addc_co_u32_e32 v17, vcc, 0, v7, vcc
	v_add_co_u32_e32 v18, vcc, s41, v6
	s_nop 1
	v_addc_co_u32_e32 v19, vcc, 0, v7, vcc
	global_load_dword v35, v[16:17], off offset:2048
	global_load_dword v36, v[18:19], off offset:2048
	global_load_dword v37, v[18:19], off
	global_load_dword v38, v[16:17], off
	global_load_dword v39, v[14:15], off
	global_load_dword v40, v[10:11], off
	v_add_co_u32_e32 v10, vcc, s42, v6
	ds_read2st64_b32 v[20:21], v32 offset0:24 offset1:28
	s_nop 0
	v_addc_co_u32_e32 v11, vcc, 0, v7, vcc
	v_add_co_u32_e32 v16, vcc, s43, v6
	s_nop 1
	v_addc_co_u32_e32 v17, vcc, 0, v7, vcc
	v_add_co_u32_e32 v18, vcc, s44, v6
	s_nop 1
	v_addc_co_u32_e32 v19, vcc, 0, v7, vcc
	global_load_dword v41, v[6:7], off offset:2048
	global_load_dword v42, v[10:11], off offset:2048
	global_load_dword v43, v[16:17], off offset:2048
	global_load_dword v44, v[18:19], off offset:2048
	global_load_dword v45, v[6:7], off
	global_load_dword v46, v[18:19], off
	global_load_dword v47, v[16:17], off
	global_load_dword v48, v[10:11], off
	v_lshlrev_b32_e32 v18, 16, v3
	v_and_b32_e32 v19, 0xffff0000, v3
	v_lshlrev_b32_e32 v3, 16, v1
	v_and_b32_e32 v1, 0xffff0000, v1
	v_mul_f32_e32 v3, 0x3fb8aa3b, v3
	v_mul_f32_e32 v1, 0x3fb8aa3b, v1
	v_exp_f32_e32 v24, v3
	v_exp_f32_e32 v25, v1
	s_waitcnt lgkmcnt(0)
	v_lshlrev_b32_e32 v16, 16, v21
	v_and_b32_e32 v17, 0xffff0000, v21
	s_waitcnt vmcnt(17)
	v_lshlrev_b32_e32 v21, 16, v26
	v_and_b32_e32 v1, 0xffff0000, v26
	v_mul_f32_e32 v3, 0x3fb8aa3b, v21
	v_mul_f32_e32 v1, 0x3fb8aa3b, v1
	v_exp_f32_e32 v26, v3
	v_pk_fma_f32 v[4:5], v[4:5], v[24:25], v[22:23]
	v_exp_f32_e32 v27, v1
	v_pk_add_f32 v[16:17], v[4:5], v[16:17]
	s_nop 0
	v_pk_mul_f32 v[16:17], v[16:17], v[18:19]
	v_lshlrev_b32_e32 v18, 16, v29
	v_cvt_pk_bf16_f32 v3, v16, v17
	v_lshlrev_b32_e32 v16, 16, v30
	v_and_b32_e32 v17, 0xffff0000, v30
	v_pk_fma_f32 v[4:5], v[4:5], v[26:27], v[16:17]
	v_lshlrev_b32_e32 v16, 16, v20
	v_and_b32_e32 v17, 0xffff0000, v20
	global_store_dword v[8:9], v3, off offset:2048 sc1
	v_and_b32_e32 v19, 0xffff0000, v29
	v_pk_add_f32 v[16:17], v[4:5], v[16:17]
	s_waitcnt vmcnt(17)
	v_lshlrev_b32_e32 v3, 16, v31
	v_pk_mul_f32 v[16:17], v[16:17], v[18:19]
	v_mul_f32_e32 v3, 0x3fb8aa3b, v3
	v_cvt_pk_bf16_f32 v1, v16, v17
	v_exp_f32_e32 v16, v3
	v_and_b32_e32 v3, 0xffff0000, v31
	v_mul_f32_e32 v3, 0x3fb8aa3b, v3
	ds_read2st64_b32 v[18:19], v32 offset0:16 offset1:20
	v_exp_f32_e32 v17, v3
	global_store_dword v[8:9], v1, off sc1
	v_lshlrev_b32_e32 v3, 16, v28
	v_mul_f32_e32 v3, 0x3fb8aa3b, v3
	s_waitcnt vmcnt(17)
	v_lshlrev_b32_e32 v8, 16, v33
	v_and_b32_e32 v9, 0xffff0000, v33
	v_pk_fma_f32 v[4:5], v[4:5], v[16:17], v[8:9]
	s_waitcnt lgkmcnt(0)
	v_lshlrev_b32_e32 v8, 16, v19
	v_and_b32_e32 v9, 0xffff0000, v19
	v_pk_add_f32 v[8:9], v[4:5], v[8:9]
	s_waitcnt vmcnt(16)
	v_lshlrev_b32_e32 v16, 16, v34
	v_and_b32_e32 v17, 0xffff0000, v34
	v_pk_mul_f32 v[8:9], v[8:9], v[16:17]
	s_waitcnt vmcnt(10)
	v_lshlrev_b32_e32 v16, 16, v40
	v_cvt_pk_bf16_f32 v1, v8, v9
	v_exp_f32_e32 v8, v3
	v_and_b32_e32 v3, 0xffff0000, v28
	v_mul_f32_e32 v3, 0x3fb8aa3b, v3
	v_exp_f32_e32 v9, v3
	v_and_b32_e32 v17, 0xffff0000, v40
	v_lshlrev_b32_e32 v3, 16, v35
	v_mul_f32_e32 v3, 0x3fb8aa3b, v3
	v_pk_fma_f32 v[4:5], v[4:5], v[8:9], v[16:17]
	v_lshlrev_b32_e32 v8, 16, v18
	v_and_b32_e32 v9, 0xffff0000, v18
	v_lshlrev_b32_e32 v16, 16, v39
	v_and_b32_e32 v17, 0xffff0000, v39
	v_pk_add_f32 v[8:9], v[4:5], v[8:9]
	global_store_dword v[14:15], v1, off offset:2048 sc1
	v_pk_mul_f32 v[8:9], v[8:9], v[16:17]
	ds_read2st64_b32 v[16:17], v32 offset0:8 offset1:12
	v_cvt_pk_bf16_f32 v1, v8, v9
	v_exp_f32_e32 v8, v3
	v_and_b32_e32 v3, 0xffff0000, v35
	v_mul_f32_e32 v3, 0x3fb8aa3b, v3
	v_exp_f32_e32 v9, v3
	global_store_dword v[14:15], v1, off sc1
	v_lshlrev_b32_e32 v14, 16, v36
	v_and_b32_e32 v15, 0xffff0000, v36
	v_pk_fma_f32 v[4:5], v[4:5], v[8:9], v[14:15]
	s_waitcnt lgkmcnt(0)
	v_lshlrev_b32_e32 v8, 16, v17
	v_and_b32_e32 v9, 0xffff0000, v17
	s_waitcnt vmcnt(10)
	v_lshlrev_b32_e32 v14, 16, v42
	v_and_b32_e32 v15, 0xffff0000, v42
	v_pk_add_f32 v[8:9], v[4:5], v[8:9]
	v_lshlrev_b32_e32 v3, 16, v38
	v_pk_mul_f32 v[8:9], v[8:9], v[14:15]
	v_mul_f32_e32 v3, 0x3fb8aa3b, v3
	v_cvt_pk_bf16_f32 v1, v8, v9
	v_exp_f32_e32 v8, v3
	v_and_b32_e32 v3, 0xffff0000, v38
	v_mul_f32_e32 v3, 0x3fb8aa3b, v3
	v_exp_f32_e32 v9, v3
	v_lshlrev_b32_e32 v14, 16, v37
	v_and_b32_e32 v15, 0xffff0000, v37
	s_waitcnt vmcnt(9)
	v_lshlrev_b32_e32 v3, 16, v43
	v_pk_fma_f32 v[4:5], v[4:5], v[8:9], v[14:15]
	v_lshlrev_b32_e32 v8, 16, v16
	v_and_b32_e32 v9, 0xffff0000, v16
	s_waitcnt vmcnt(4)
	v_lshlrev_b32_e32 v14, 16, v48
	v_and_b32_e32 v15, 0xffff0000, v48
	v_pk_add_f32 v[8:9], v[4:5], v[8:9]
	v_mul_f32_e32 v3, 0x3fb8aa3b, v3
	v_pk_mul_f32 v[8:9], v[8:9], v[14:15]
	global_store_dword v[10:11], v1, off offset:2048 sc1
	v_cvt_pk_bf16_f32 v1, v8, v9
	v_exp_f32_e32 v8, v3
	v_and_b32_e32 v3, 0xffff0000, v43
	v_mul_f32_e32 v3, 0x3fb8aa3b, v3
	ds_read2st64_b32 v[14:15], v32 offset1:4
	v_exp_f32_e32 v9, v3
	global_store_dword v[10:11], v1, off sc1
	v_lshlrev_b32_e32 v10, 16, v44
	v_and_b32_e32 v11, 0xffff0000, v44
	v_pk_fma_f32 v[4:5], v[4:5], v[8:9], v[10:11]
	s_waitcnt lgkmcnt(0)
	v_lshlrev_b32_e32 v8, 16, v15
	v_and_b32_e32 v9, 0xffff0000, v15
	v_lshlrev_b32_e32 v10, 16, v41
	v_and_b32_e32 v11, 0xffff0000, v41
	v_pk_add_f32 v[8:9], v[4:5], v[8:9]
	v_lshlrev_b32_e32 v3, 16, v47
	v_pk_mul_f32 v[8:9], v[8:9], v[10:11]
	v_mul_f32_e32 v3, 0x3fb8aa3b, v3
	v_cvt_pk_bf16_f32 v1, v8, v9
	v_exp_f32_e32 v8, v3
	v_and_b32_e32 v3, 0xffff0000, v47
	v_mul_f32_e32 v3, 0x3fb8aa3b, v3
	v_exp_f32_e32 v9, v3
	v_lshlrev_b32_e32 v10, 16, v46
	v_and_b32_e32 v11, 0xffff0000, v46
	global_store_dword v[6:7], v1, off offset:2048 sc1
	v_pk_fma_f32 v[4:5], v[4:5], v[8:9], v[10:11]
	v_lshlrev_b32_e32 v8, 16, v14
	v_and_b32_e32 v9, 0xffff0000, v14
	v_lshlrev_b32_e32 v10, 16, v45
	v_and_b32_e32 v11, 0xffff0000, v45
	v_pk_add_f32 v[8:9], v[4:5], v[8:9]
	s_nop 0
	v_pk_mul_f32 v[8:9], v[8:9], v[10:11]
	s_nop 0
	v_cvt_pk_bf16_f32 v1, v8, v9
	global_store_dword v[6:7], v1, off sc1
	v_lshl_add_u64 v[6:7], v[6:7], 0, s[20:21]
	s_cbranch_scc0 .LBB0_1546
	s_cmp_eq_u32 s46, s48
	s_cselect_b64 s[0:1], -1, 0
	s_and_b64 s[0:1], s[22:23], s[0:1]
	s_and_b64 vcc, exec, s[0:1]
	s_cbranch_vccz .LBB0_1528
	s_lshl_b32 s0, s47, 11
	s_ashr_i32 s1, s0, 31
	s_lshl_b64 s[0:1], s[0:1], 2
	s_add_u32 s0, s12, s0
	s_addc_u32 s1, s13, s1
	v_mov_b32_e32 v3, v0
	v_lshl_add_u64 v[2:3], s[0:1], 0, v[2:3]
	v_add_co_u32_e32 v2, vcc, 0x9a01000, v2
	s_nop 1
	v_addc_co_u32_e32 v3, vcc, 0, v3, vcc
	global_store_dwordx2 v[2:3], v[4:5], off sc1
	s_branch .LBB0_1528
.LBB0_1549:
	s_cmp_gt_i32 s17, 24
	s_cselect_b64 s[0:1], -1, 0
	s_and_b64 s[4:5], s[4:5], s[0:1]
	s_andn2_b64 vcc, exec, s[4:5]
	s_cbranch_vccnz .LBB0_1561
	s_waitcnt vmcnt(0)
	v_or_b32_e32 v0, v201, v200
	s_movk_i32 s3, 0x3ff
	v_and_or_b32 v0, v0, s3, v199
	v_cmp_eq_u32_e32 vcc, 0, v0
	s_waitcnt lgkmcnt(0)
	s_barrier
	s_and_saveexec_b64 s[4:5], vcc
	s_cbranch_execz .LBB0_1560
	s_add_u32 s6, s14, 0x5be8c00
	s_addc_u32 s7, s15, 0
	s_lshl_b32 s3, s2, 1
	v_mov_b32_e32 v0, s3
	v_mov_b32_e32 v1, 0x9318
	global_store_short v0, v1, s[6:7] sc1
	s_cmp_lg_u32 s2, 0
	s_cbranch_scc1 .Lgbar_wait_23
	s_lshr_b32 s3, s33, 3
	s_bfm_b64 s[8:9], s3, 0
	s_cmpk_gt_u32 s33, 0x1ff
	s_cselect_b64 s[8:9], -1, s[8:9]
	s_mov_b64 exec, -1
	v_mbcnt_lo_u32_b32 v229, -1, 0
	v_mbcnt_hi_u32_b32 v229, -1, v229
	v_lshlrev_b32_e32 v229, 4, v229
	s_mov_b32 s10, 0x93189318
	s_mov_b64 exec, s[8:9]

.LBB0_1561:
	s_cmp_lt_i32 s16, 25
	s_cselect_b64 s[4:5], -1, 0
	s_and_b64 s[0:1], s[4:5], s[0:1]
	s_andn2_b64 vcc, exec, s[0:1]
	s_cbranch_vccnz .LBB0_1601
	s_ashr_i32 s0, s2, 31
	s_and_b32 s0, s0, s33
	s_add_i32 s3, s0, s2
	s_cmpk_gt_i32 s3, 0x3ff
	s_cbranch_scc1 .LBB0_1601
	v_lshrrev_b32_e32 v0, 3, v199
	s_waitcnt lgkmcnt(0)
	v_lshrrev_b32_e32 v1, 5, v199
	v_bfe_u32 v4, v199, 1, 3
	v_lshlrev_b32_e32 v5, 4, v199
	v_bfe_u32 v2, v199, 5, 1
	v_xor_b32_e32 v6, v5, v199
	v_lshlrev_b32_e32 v7, 11, v0
	s_movk_i32 s0, 0x70
	v_bitop3_b32 v1, v1, v4, 1 bitop3:0x6c
	v_and_or_b32 v64, v6, s0, v7
	v_lshlrev_b32_e32 v7, 4, v1
	v_bitop3_b32 v1, v2, v4, 2 bitop3:0x36
	v_lshrrev_b32_e32 v3, 1, v199
	v_lshlrev_b32_e32 v9, 4, v1
	v_bitop3_b32 v1, v2, v4, 4 bitop3:0x36
	v_mov_b32_e32 v65, 0
	v_and_b32_e32 v3, 0x1e0, v3
	v_lshlrev_b32_e32 v10, 4, v1
	v_bitop3_b32 v1, v2, v4, 6 bitop3:0x36
	s_waitcnt vmcnt(25)
	v_and_b32_e32 v138, 31, v199
	v_lshlrev_b32_e32 v2, 4, v1
	v_and_or_b32 v139, v0, 4, v3
	v_lshl_add_u64 v[0:1], s[14:15], 0, v[64:65]
	s_mov_b64 s[8:9], 0xdf9f000
	s_add_u32 s10, s14, 0x5c4e000
	v_or_b32_e32 v6, v3, v138
	v_lshl_add_u64 v[66:67], v[0:1], 0, s[8:9]
	s_mov_b64 s[8:9], 0x17a0000
	s_addc_u32 s11, s15, 0
	v_lshl_add_u32 v6, v6, 7, 0
	v_lshl_add_u32 v8, v138, 7, 0
	v_lshl_add_u64 v[68:69], v[0:1], 0, s[8:9]
	s_add_u32 s8, s14, 0x679f000
	v_add_u32_e32 v140, 0, v5
	v_mbcnt_lo_u32_b32 v0, -1, 0
	s_mov_b32 s7, 0
	v_cmp_eq_u32_e64 s[0:1], 0, v138
	s_addc_u32 s9, s15, 0
	v_add_u32_e32 v141, 0x4000, v140
	s_mov_b64 s[18:19], 0x10000
	v_add_u32_e32 v142, 0x1000, v140
	v_add_u32_e32 v143, 0x5000, v140
	s_mov_b64 s[20:21], 0x20000
	s_waitcnt vmcnt(24)
	v_add_u32_e32 v144, 0x2000, v140
	v_add_u32_e32 v145, 0x6000, v140
	s_mov_b64 s[22:23], 0x30000
	v_add_u32_e32 v146, 0x3000, v140
	v_add_u32_e32 v147, 0x7000, v140
	s_mov_b64 s[24:25], 0xdf9f080
	s_mov_b64 s[26:27], 0x17a0080
	v_add_u32_e32 v148, 0x8000, v140
	v_add_u32_e32 v149, 0xc000, v140
	s_mov_b64 s[28:29], 0xdfaf080
	v_add_u32_e32 v150, 0x9000, v140
	s_mov_b64 s[30:31], 0x17b0080
	v_add_u32_e32 v151, 0xd000, v140
	s_mov_b64 s[34:35], 0xdfbf080
	s_waitcnt vmcnt(23)
	v_add_u32_e32 v152, 0xa000, v140
	s_mov_b64 s[36:37], 0x17c0080
	v_add_u32_e32 v153, 0xe000, v140
	s_mov_b64 s[38:39], 0xdfcf080
	v_add_u32_e32 v154, 0xb000, v140
	s_mov_b64 s[40:41], 0x17d0080
	v_add_u32_e32 v155, 0xf000, v140
	s_waitcnt vmcnt(22)
	v_add_u32_e32 v156, v6, v7
	v_add_u32_e32 v157, v8, v7
	v_add_u32_e32 v158, v6, v9
	v_add_u32_e32 v159, v8, v9
	s_waitcnt vmcnt(21)
	v_add_u32_e32 v160, v6, v10
	v_add_u32_e32 v161, v8, v10
	v_add_u32_e32 v162, v6, v2
	v_add_u32_e32 v163, v8, v2
	s_mov_b64 s[42:43], 0xdf9f100
	s_mov_b64 s[44:45], 0x17a0100
	s_mov_b64 s[46:47], 0xdfaf100
	s_mov_b64 s[48:49], 0x17b0100
	s_mov_b64 s[50:51], 0xdfbf100
	s_mov_b64 s[52:53], 0x17c0100
	s_mov_b64 s[54:55], 0xdfcf100
	s_mov_b64 s[56:57], 0x17d0100
	s_add_i32 s70, 0, 0x12070
	s_waitcnt vmcnt(19)
	v_mbcnt_hi_u32_b32 v164, -1, v0
	s_mov_b32 s39, 0
	s_branch .LBB0_1565

.LBB0_1565:
	s_ashr_i32 s6, s3, 31
	s_lshr_b32 s6, s6, 26
	s_add_i32 s6, s3, s6
	s_ashr_i32 s58, s6, 6
	s_andn2_b32 s6, s6, 63
	s_sub_i32 s6, s3, s6
	s_ashr_i32 s59, s6, 31
	s_lshr_b32 s59, s59, 29
	s_add_i32 s59, s6, s59
	s_ashr_i32 s64, s59, 3
	s_and_b32 s59, s59, -8
	s_lshl_b32 s58, s58, 3
	s_sub_i32 s6, s6, s59
	s_add_i32 s6, s6, s58
	s_lshl_b32 s66, s6, 7
	s_ashr_i32 s67, s66, 31
	s_lshl_b32 s68, s64, 7
	s_lshl_b64 s[58:59], s[66:67], 11
	s_ashr_i32 s69, s68, 31
	s_cmp_eq_u32 s39, 1
	s_cbranch_scc1 .Lgk_pfhead_p24
	s_lshl_b32 s38, s66, 11
	s_add_u32 s18, s14, s38
	s_addc_u32 s19, s15, 0
	s_add_u32 s18, s18, 0xdf9f000
	s_addc_u32 s19, s19, 0
	s_add_u32 s20, s18, 0x10000
	s_addc_u32 s21, s19, 0
	s_add_u32 s22, s20, 0x10000
	s_addc_u32 s23, s21, 0
	s_add_u32 s24, s22, 0x10000
	s_addc_u32 s25, s23, 0
	s_lshl_b32 s38, s68, 11
	s_add_u32 s26, s14, s38
	s_addc_u32 s27, s15, 0
	s_add_u32 s26, s26, 0x17a0000
	s_addc_u32 s27, s27, 0
	s_add_u32 s28, s26, 0x10000
	s_addc_u32 s29, s27, 0
	s_add_u32 s30, s28, 0x10000
	s_addc_u32 s31, s29, 0
	s_add_u32 s34, s30, 0x10000
	s_addc_u32 s35, s31, 0
	v_readfirstlane_b32 s36, v140
	v_mov_b32_e32 v254, v64
	s_mov_b32 m0, s36
	s_nop 0
	global_load_lds_dwordx4 v254, s[18:19]
	s_add_u32 m0, m0, 0x1000
	s_nop 0
	global_load_lds_dwordx4 v254, s[20:21]
	s_add_u32 m0, m0, 0x1000
	s_nop 0
	global_load_lds_dwordx4 v254, s[22:23]
	s_add_u32 m0, m0, 0x1000
	s_nop 0
	global_load_lds_dwordx4 v254, s[24:25]
	s_add_u32 m0, m0, 0x1000
	s_nop 0
	global_load_lds_dwordx4 v254, s[26:27]
	s_add_u32 m0, m0, 0x1000
	s_nop 0
	global_load_lds_dwordx4 v254, s[28:29]
	s_add_u32 m0, m0, 0x1000
	s_nop 0
	global_load_lds_dwordx4 v254, s[30:31]
	s_add_u32 m0, m0, 0x1000
	s_nop 0
	global_load_lds_dwordx4 v254, s[34:35]
	v_add_u32_e32 v254, 0x80, v254
	s_add_u32 m0, s36, 0x8000
	s_nop 0
	global_load_lds_dwordx4 v254, s[18:19]
	s_add_u32 m0, m0, 0x1000
	s_nop 0
	global_load_lds_dwordx4 v254, s[20:21]
	s_add_u32 m0, m0, 0x1000
	s_nop 0
	global_load_lds_dwordx4 v254, s[22:23]
	s_add_u32 m0, m0, 0x1000
	s_nop 0
	global_load_lds_dwordx4 v254, s[24:25]
	s_add_u32 m0, m0, 0x1000
	s_nop 0
	global_load_lds_dwordx4 v254, s[26:27]
	s_add_u32 m0, m0, 0x1000
	s_nop 0
	global_load_lds_dwordx4 v254, s[28:29]
	s_add_u32 m0, m0, 0x1000
	s_nop 0
	global_load_lds_dwordx4 v254, s[30:31]
	s_add_u32 m0, m0, 0x1000
	s_nop 0
	global_load_lds_dwordx4 v254, s[34:35]
	v_add_u32_e32 v254, 0x80, v254

.LBB0_1565_pf_p24:
	s_ashr_i32 s41, s40, 31
	s_lshr_b32 s41, s41, 26
	s_add_i32 s41, s40, s41
	s_ashr_i32 s42, s41, 6
	s_andn2_b32 s41, s41, 63
	s_sub_i32 s41, s40, s41
	s_ashr_i32 s43, s41, 31
	s_lshr_b32 s43, s43, 29
	s_add_i32 s43, s41, s43
	s_ashr_i32 s46, s43, 3
	s_and_b32 s43, s43, -8
	s_lshl_b32 s42, s42, 3
	s_sub_i32 s41, s41, s43
	s_add_i32 s41, s41, s42
	s_lshl_b32 s44, s41, 7
	s_ashr_i32 s45, s44, 31
	s_lshl_b32 s47, s46, 7
	s_lshl_b64 s[42:43], s[44:45], 11
	s_ashr_i32 s48, s47, 31
	s_lshl_b32 s38, s44, 11
	s_add_u32 s18, s14, s38
	s_addc_u32 s19, s15, 0
	s_add_u32 s18, s18, 0xdf9f000
	s_addc_u32 s19, s19, 0
	s_add_u32 s20, s18, 0x10000
	s_addc_u32 s21, s19, 0
	s_add_u32 s22, s20, 0x10000
	s_addc_u32 s23, s21, 0
	s_add_u32 s24, s22, 0x10000
	s_addc_u32 s25, s23, 0
	s_lshl_b32 s38, s47, 11
	s_add_u32 s26, s14, s38
	s_addc_u32 s27, s15, 0
	s_add_u32 s26, s26, 0x17a0000
	s_addc_u32 s27, s27, 0
	s_add_u32 s28, s26, 0x10000
	s_addc_u32 s29, s27, 0
	s_add_u32 s30, s28, 0x10000
	s_addc_u32 s31, s29, 0
	s_add_u32 s34, s30, 0x10000
	s_addc_u32 s35, s31, 0
	v_mov_b32_e32 v254, v64
	s_mov_b32 s39, 1
	s_waitcnt vmcnt(8)
	s_barrier
	ds_read_b128 v[70:73], v156
	ds_read_b128 v[74:77], v157 offset:16384
	ds_read_b128 v[78:81], v157 offset:20480
	ds_read_b128 v[82:85], v157 offset:24576
	ds_read_b128 v[86:89], v157 offset:28672
	ds_read_b128 v[90:93], v158
	ds_read_b128 v[94:97], v159 offset:16384
	ds_read_b128 v[98:101], v159 offset:20480
	ds_read_b128 v[102:105], v159 offset:24576
	ds_read_b128 v[106:109], v159 offset:28672
	ds_read_b128 v[110:113], v160
	ds_read_b128 v[202:205], v161 offset:16384
	ds_read_b128 v[206:209], v161 offset:20480
	ds_read_b128 v[210:213], v161 offset:24576
	ds_read_b128 v[214:217], v161 offset:28672
	ds_read_b128 v[218:221], v162
	ds_read_b128 v[222:225], v163 offset:16384
	ds_read_b128 v[226:229], v163 offset:20480
	ds_read_b128 v[230:233], v163 offset:24576
	ds_read_b128 v[234:237], v163 offset:28672
	s_waitcnt lgkmcnt(0)
	s_barrier
	s_mov_b32 m0, s36
	s_setprio 1
	v_mfma_f32_32x32x16_bf16 v[48:63], v[70:73], v[74:77], v[48:63]
	v_mfma_f32_32x32x16_bf16 v[32:47], v[70:73], v[78:81], v[32:47]
	global_load_lds_dwordx4 v254, s[18:19]
	s_add_u32 m0, m0, 0x1000
	v_mfma_f32_32x32x16_bf16 v[16:31], v[70:73], v[82:85], v[16:31]
	v_mfma_f32_32x32x16_bf16 v[0:15], v[70:73], v[86:89], v[0:15]
	global_load_lds_dwordx4 v254, s[20:21]
	s_add_u32 m0, m0, 0x1000
	v_mfma_f32_32x32x16_bf16 v[48:63], v[90:93], v[94:97], v[48:63]
	v_mfma_f32_32x32x16_bf16 v[32:47], v[90:93], v[98:101], v[32:47]
	global_load_lds_dwordx4 v254, s[22:23]
	s_add_u32 m0, m0, 0x1000
	v_mfma_f32_32x32x16_bf16 v[16:31], v[90:93], v[102:105], v[16:31]
	v_mfma_f32_32x32x16_bf16 v[0:15], v[90:93], v[106:109], v[0:15]
	global_load_lds_dwordx4 v254, s[24:25]
	s_add_u32 m0, m0, 0x1000
	v_mfma_f32_32x32x16_bf16 v[48:63], v[110:113], v[202:205], v[48:63]
	v_mfma_f32_32x32x16_bf16 v[32:47], v[110:113], v[206:209], v[32:47]
	global_load_lds_dwordx4 v254, s[26:27]
	s_add_u32 m0, m0, 0x1000
	v_mfma_f32_32x32x16_bf16 v[16:31], v[110:113], v[210:213], v[16:31]
	v_mfma_f32_32x32x16_bf16 v[0:15], v[110:113], v[214:217], v[0:15]
	global_load_lds_dwordx4 v254, s[28:29]
	s_add_u32 m0, m0, 0x1000
	v_mfma_f32_32x32x16_bf16 v[48:63], v[218:221], v[222:225], v[48:63]
	v_mfma_f32_32x32x16_bf16 v[32:47], v[218:221], v[226:229], v[32:47]
	global_load_lds_dwordx4 v254, s[30:31]
	s_add_u32 m0, m0, 0x1000
	v_mfma_f32_32x32x16_bf16 v[16:31], v[218:221], v[230:233], v[16:31]
	v_mfma_f32_32x32x16_bf16 v[0:15], v[218:221], v[234:237], v[0:15]
	global_load_lds_dwordx4 v254, s[34:35]
	s_setprio 0
	v_add_u32_e32 v254, 0x80, v254
	s_waitcnt vmcnt(8)
	s_barrier
	ds_read_b128 v[70:73], v156 offset:32768
	ds_read_b128 v[74:77], v157 offset:49152
	ds_read_b128 v[78:81], v157 offset:53248
	ds_read_b128 v[82:85], v157 offset:57344
	ds_read_b128 v[86:89], v157 offset:61440
	ds_read_b128 v[90:93], v158 offset:32768
	ds_read_b128 v[94:97], v159 offset:49152
	ds_read_b128 v[98:101], v159 offset:53248
	ds_read_b128 v[102:105], v159 offset:57344
	ds_read_b128 v[106:109], v159 offset:61440
	ds_read_b128 v[110:113], v160 offset:32768
	ds_read_b128 v[202:205], v161 offset:49152
	ds_read_b128 v[206:209], v161 offset:53248
	ds_read_b128 v[210:213], v161 offset:57344
	ds_read_b128 v[214:217], v161 offset:61440
	ds_read_b128 v[218:221], v162 offset:32768
	ds_read_b128 v[222:225], v163 offset:49152
	ds_read_b128 v[226:229], v163 offset:53248
	ds_read_b128 v[230:233], v163 offset:57344
	ds_read_b128 v[234:237], v163 offset:61440
	s_waitcnt lgkmcnt(0)
	s_barrier
	s_add_u32 m0, s36, 0x8000
	s_setprio 1
	v_mfma_f32_32x32x16_bf16 v[48:63], v[70:73], v[74:77], v[48:63]
	v_mfma_f32_32x32x16_bf16 v[32:47], v[70:73], v[78:81], v[32:47]
	global_load_lds_dwordx4 v254, s[18:19]
	s_add_u32 m0, m0, 0x1000
	v_mfma_f32_32x32x16_bf16 v[16:31], v[70:73], v[82:85], v[16:31]
	v_mfma_f32_32x32x16_bf16 v[0:15], v[70:73], v[86:89], v[0:15]
	global_load_lds_dwordx4 v254, s[20:21]
	s_add_u32 m0, m0, 0x1000
	v_mfma_f32_32x32x16_bf16 v[48:63], v[90:93], v[94:97], v[48:63]
	v_mfma_f32_32x32x16_bf16 v[32:47], v[90:93], v[98:101], v[32:47]
	global_load_lds_dwordx4 v254, s[22:23]
	s_add_u32 m0, m0, 0x1000
	v_mfma_f32_32x32x16_bf16 v[16:31], v[90:93], v[102:105], v[16:31]
	v_mfma_f32_32x32x16_bf16 v[0:15], v[90:93], v[106:109], v[0:15]
	global_load_lds_dwordx4 v254, s[24:25]
	s_add_u32 m0, m0, 0x1000
	v_mfma_f32_32x32x16_bf16 v[48:63], v[110:113], v[202:205], v[48:63]
	v_mfma_f32_32x32x16_bf16 v[32:47], v[110:113], v[206:209], v[32:47]
	global_load_lds_dwordx4 v254, s[26:27]
	s_add_u32 m0, m0, 0x1000
	v_mfma_f32_32x32x16_bf16 v[16:31], v[110:113], v[210:213], v[16:31]
	v_mfma_f32_32x32x16_bf16 v[0:15], v[110:113], v[214:217], v[0:15]
	global_load_lds_dwordx4 v254, s[28:29]
	s_add_u32 m0, m0, 0x1000
	v_mfma_f32_32x32x16_bf16 v[48:63], v[218:221], v[222:225], v[48:63]
	v_mfma_f32_32x32x16_bf16 v[32:47], v[218:221], v[226:229], v[32:47]
	global_load_lds_dwordx4 v254, s[30:31]
	s_add_u32 m0, m0, 0x1000
	v_mfma_f32_32x32x16_bf16 v[16:31], v[218:221], v[230:233], v[16:31]
	v_mfma_f32_32x32x16_bf16 v[0:15], v[218:221], v[234:237], v[0:15]
	global_load_lds_dwordx4 v254, s[34:35]
	s_setprio 0
	v_add_u32_e32 v254, 0x80, v254
	s_branch .LBB0_1569

.LBB0_1569:
	s_add_i32 s58, s66, 0xffffe000
	s_lshr_b32 s58, s58, 12
	s_mulk_i32 s58, 0x1800
	v_mov_b32_e32 v70, s70
	s_add_i32 s58, s58, 0xf000
	ds_read_b64 v[70:71], v70
	s_cmp_gt_i32 s6, 63
	s_cselect_b32 s6, s58, 0xd800
	s_lshl_b64 s[58:59], s[6:7], 2
	s_add_u32 s6, s14, s58
	s_addc_u32 s65, s15, s59
	s_waitcnt lgkmcnt(0)
	v_readfirstlane_b32 s58, v70
	v_readfirstlane_b32 s59, v71
	s_add_u32 s60, s58, 0x3000
	s_addc_u32 s61, s59, 0
	s_lshl_b32 s58, s64, 14
	s_add_i32 s58, s58, 0xe0000
	s_ashr_i32 s59, s58, 31
	s_lshl_b64 s[58:59], s[58:59], 2
	s_add_u32 s58, s10, s58
	s_addc_u32 s59, s11, s59
	s_add_u32 s62, s6, 0x5ba2000
	v_or_b32_e32 v102, s68, v138
	v_add_u32_e32 v70, s66, v139
	s_addc_u32 s63, s65, 0
	v_lshlrev_b32_e32 v188, 10, v70
	v_ashrrev_i32_e32 v103, 31, v102
	s_add_u32 s64, s6, 0x5ba4000
	v_lshlrev_b64 v[72:73], 2, v[102:103]
	v_or_b32_e32 v186, 0x400, v188
	v_or_b32_e32 v185, 0x4400, v188
	v_or_b32_e32 v189, 0x4c00, v188
	v_or_b32_e32 v193, 0x6c00, v188
	s_addc_u32 s65, s65, 0
	v_lshl_add_u64 v[74:75], s[62:63], 0, v[72:73]
	v_add_u32_e32 v132, v188, v102
	v_add_u32_e32 v134, v186, v102
	v_or_b32_e32 v184, 0x800, v188
	v_or_b32_e32 v183, 0xc00, v188
	v_or_b32_e32 v181, 0x2000, v188
	v_or_b32_e32 v179, 0x2400, v188
	v_or_b32_e32 v71, 0x2800, v188
	v_or_b32_e32 v180, 0x2c00, v188
	v_or_b32_e32 v182, 0x4000, v188
	v_add_u32_e32 v112, v185, v102
	v_or_b32_e32 v187, 0x4800, v188
	v_add_u32_e32 v118, v189, v102
	v_or_b32_e32 v190, 0x6000, v188
	v_or_b32_e32 v191, 0x6400, v188
	v_or_b32_e32 v192, 0x6800, v188
	v_add_u32_e32 v128, v193, v102
	global_load_dword v194, v[74:75], off
	v_lshl_add_u64 v[74:75], s[60:61], 0, v[72:73]
	v_lshl_add_u64 v[72:73], s[64:65], 0, v[72:73]
	v_ashrrev_i32_e32 v135, 31, v134
	v_add_u32_e32 v136, v184, v102
	v_add_u32_e32 v130, v183, v102
	v_add_u32_e32 v122, v181, v102
	v_add_u32_e32 v114, v179, v102
	v_add_u32_e32 v106, v71, v102
	v_add_u32_e32 v108, v180, v102
	v_add_u32_e32 v110, v182, v102
	v_ashrrev_i32_e32 v113, 31, v112
	v_add_u32_e32 v116, v187, v102
	v_ashrrev_i32_e32 v119, 31, v118
	v_add_u32_e32 v120, v190, v102
	v_add_u32_e32 v124, v191, v102
	v_add_u32_e32 v126, v192, v102
	v_ashrrev_i32_e32 v129, 31, v128
	v_ashrrev_i32_e32 v133, 31, v132
	global_load_dword v196, v[72:73], off
	v_lshl_add_u64 v[88:89], v[134:135], 2, s[12:13]
	v_ashrrev_i32_e32 v137, 31, v136
	v_ashrrev_i32_e32 v131, 31, v130
	v_ashrrev_i32_e32 v123, 31, v122
	v_ashrrev_i32_e32 v115, 31, v114
	v_ashrrev_i32_e32 v107, 31, v106
	v_ashrrev_i32_e32 v109, 31, v108
	v_ashrrev_i32_e32 v111, 31, v110
	v_lshl_add_u64 v[86:87], v[112:113], 2, s[12:13]
	v_ashrrev_i32_e32 v117, 31, v116
	v_lshl_add_u64 v[92:93], v[118:119], 2, s[12:13]
	v_ashrrev_i32_e32 v121, 31, v120
	v_ashrrev_i32_e32 v125, 31, v124
	v_ashrrev_i32_e32 v127, 31, v126
	v_lshl_add_u64 v[100:101], v[128:129], 2, s[12:13]
	v_lshl_add_u64 v[104:105], v[132:133], 2, s[12:13]
	global_load_dword v195, v[74:75], off
	v_lshl_add_u64 v[84:85], v[136:137], 2, s[12:13]
	v_lshl_add_u64 v[82:83], v[130:131], 2, s[12:13]
	v_lshl_add_u64 v[78:79], v[122:123], 2, s[12:13]
	v_lshl_add_u64 v[72:73], v[114:115], 2, s[12:13]
	v_lshl_add_u64 v[74:75], v[106:107], 2, s[12:13]
	v_lshl_add_u64 v[76:77], v[108:109], 2, s[12:13]
	v_lshl_add_u64 v[80:81], v[110:111], 2, s[12:13]
	global_load_dword v178, v[88:89], off
	global_load_dword v177, v[84:85], off
	global_load_dword v176, v[82:83], off
	global_load_dword v175, v[78:79], off
	global_load_dword v174, v[72:73], off
	global_load_dword v173, v[74:75], off
	global_load_dword v172, v[76:77], off
	global_load_dword v171, v[80:81], off
	v_lshl_add_u64 v[90:91], v[116:117], 2, s[12:13]
	global_load_dword v170, v[86:87], off
	global_load_dword v168, v[90:91], off
	v_lshl_add_u64 v[94:95], v[120:121], 2, s[12:13]
	v_lshl_add_u64 v[96:97], v[124:125], 2, s[12:13]
	v_lshl_add_u64 v[98:99], v[126:127], 2, s[12:13]
	global_load_dword v169, v[92:93], off
	global_load_dword v167, v[94:95], off
	global_load_dword v166, v[96:97], off
	global_load_dword v165, v[98:99], off
	global_load_dword v103, v[100:101], off
	global_load_dword v197, v[104:105], off
	v_lshl_add_u64 v[106:107], v[106:107], 1, s[8:9]
	s_waitcnt vmcnt(0)
	v_add_f32_e32 v196, 1.0, v196
	v_mul_f32_e32 v195, v195, v196
	v_fmac_f32_e32 v178, v49, v194
	v_fmac_f32_e32 v177, v50, v194
	v_fmac_f32_e32 v176, v51, v194
	v_fmac_f32_e32 v175, v52, v194
	v_fmac_f32_e32 v174, v53, v194
	v_fmac_f32_e32 v173, v54, v194
	v_fmac_f32_e32 v172, v55, v194
	v_fmac_f32_e32 v171, v56, v194
	v_fmac_f32_e32 v170, v57, v194
	v_fmac_f32_e32 v168, v58, v194
	v_fmac_f32_e32 v169, v59, v194
	v_fmac_f32_e32 v167, v60, v194
	v_fmac_f32_e32 v166, v61, v194
	v_fmac_f32_e32 v165, v62, v194
	v_fmac_f32_e32 v103, v63, v194
	v_fmac_f32_e32 v197, v48, v194
	v_mul_f32_e32 v48, v195, v197
	v_cvt_pk_bf16_f32 v58, v48, s0
	v_or_b32_e32 v48, 32, v102
	v_ashrrev_i32_e32 v49, 31, v48
	v_lshlrev_b64 v[52:53], 2, v[48:49]
	global_store_dword v[88:89], v178, off sc1
	global_store_dword v[84:85], v177, off sc1
	global_store_dword v[82:83], v176, off sc1
	global_store_dword v[78:79], v175, off sc1
	global_store_dword v[72:73], v174, off sc1
	global_store_dword v[74:75], v173, off sc1
	global_store_dword v[76:77], v172, off sc1
	global_store_dword v[80:81], v171, off sc1
	global_store_dword v[86:87], v170, off sc1
	global_store_dword v[90:91], v168, off sc1
	global_store_dword v[92:93], v169, off sc1
	global_store_dword v[94:95], v167, off sc1
	global_store_dword v[96:97], v166, off sc1
	global_store_dword v[98:99], v165, off sc1
	global_store_dword v[100:101], v103, off sc1
	global_store_dword v[104:105], v197, off sc1
	v_lshl_add_u64 v[50:51], v[132:133], 1, s[8:9]
	v_lshl_add_u64 v[56:57], s[64:65], 0, v[52:53]
	global_load_dword v196, v[104:105], off offset:128
	v_lshl_add_u64 v[54:55], s[60:61], 0, v[52:53]
	global_load_dword v132, v[56:57], off
	global_load_dword v133, v[54:55], off
	v_mul_f32_e32 v49, v195, v178
	global_store_short v[50:51], v58, off sc1
	v_lshl_add_u64 v[50:51], s[62:63], 0, v[52:53]
	global_load_dword v194, v[50:51], off
	v_cvt_pk_bf16_f32 v49, v49, s0
	v_lshl_add_u64 v[50:51], v[134:135], 1, s[8:9]
	global_store_short v[50:51], v49, off sc1
	v_mul_f32_e32 v49, v195, v177
	v_cvt_pk_bf16_f32 v49, v49, s0
	v_lshl_add_u64 v[50:51], v[136:137], 1, s[8:9]
	global_store_short v[50:51], v49, off sc1
	v_mul_f32_e32 v49, v195, v176
	v_cvt_pk_bf16_f32 v49, v49, s0
	v_lshl_add_u64 v[50:51], v[130:131], 1, s[8:9]
	global_store_short v[50:51], v49, off sc1
	v_mul_f32_e32 v49, v195, v175
	v_cvt_pk_bf16_f32 v49, v49, s0
	v_lshl_add_u64 v[50:51], v[122:123], 1, s[8:9]
	global_store_short v[50:51], v49, off sc1
	v_mul_f32_e32 v49, v195, v174
	v_cvt_pk_bf16_f32 v49, v49, s0
	v_lshl_add_u64 v[50:51], v[114:115], 1, s[8:9]
	global_store_short v[50:51], v49, off sc1
	v_mul_f32_e32 v49, v195, v173
	global_load_dword v62, v[84:85], off offset:128
	global_load_dword v60, v[78:79], off offset:128
	global_load_dword v59, v[72:73], off offset:128
	global_load_dword v58, v[74:75], off offset:128
	global_load_dword v56, v[80:81], off offset:128
	global_load_dword v57, v[76:77], off offset:128
	global_load_dword v55, v[86:87], off offset:128
	global_load_dword v61, v[82:83], off offset:128
	global_load_dword v54, v[90:91], off offset:128
	global_load_dword v53, v[92:93], off offset:128
	global_load_dword v52, v[94:95], off offset:128
	global_load_dword v51, v[96:97], off offset:128
	global_load_dword v50, v[98:99], off offset:128
	v_cvt_pk_bf16_f32 v63, v49, s0
	global_load_dword v49, v[100:101], off offset:128
	s_waitcnt vmcnt(19)
	v_fmac_f32_e32 v196, v32, v194
	global_store_short v[106:107], v63, off sc1
	global_load_dword v63, v[88:89], off offset:128
	v_mul_f32_e32 v106, v195, v172
	v_cvt_pk_bf16_f32 v114, v106, s0
	v_lshl_add_u64 v[106:107], v[108:109], 1, s[8:9]
	global_store_short v[106:107], v114, off sc1
	v_mul_f32_e32 v106, v195, v171
	v_cvt_pk_bf16_f32 v108, v106, s0
	v_lshl_add_u64 v[106:107], v[110:111], 1, s[8:9]
	global_store_short v[106:107], v108, off sc1
	v_mul_f32_e32 v106, v195, v170
	v_cvt_pk_bf16_f32 v108, v106, s0
	v_lshl_add_u64 v[106:107], v[112:113], 1, s[8:9]
	global_store_short v[106:107], v108, off sc1
	v_mul_f32_e32 v106, v195, v168
	v_cvt_pk_bf16_f32 v108, v106, s0
	v_lshl_add_u64 v[106:107], v[116:117], 1, s[8:9]
	global_store_short v[106:107], v108, off sc1
	v_mul_f32_e32 v106, v195, v169
	v_cvt_pk_bf16_f32 v108, v106, s0
	v_lshl_add_u64 v[106:107], v[118:119], 1, s[8:9]
	global_store_short v[106:107], v108, off sc1
	v_mul_f32_e32 v106, v195, v167
	v_cvt_pk_bf16_f32 v108, v106, s0
	v_lshl_add_u64 v[106:107], v[120:121], 1, s[8:9]
	global_store_short v[106:107], v108, off sc1
	v_mul_f32_e32 v106, v195, v166
	v_cvt_pk_bf16_f32 v108, v106, s0
	v_lshl_add_u64 v[106:107], v[124:125], 1, s[8:9]
	global_store_short v[106:107], v108, off sc1
	v_mul_f32_e32 v106, v195, v165
	v_cvt_pk_bf16_f32 v108, v106, s0
	v_lshl_add_u64 v[106:107], v[126:127], 1, s[8:9]
	global_store_short v[106:107], v108, off sc1
	v_mul_f32_e32 v106, v195, v103
	v_cvt_pk_bf16_f32 v108, v106, s0
	v_lshl_add_u64 v[106:107], v[128:129], 1, s[8:9]
	global_store_short v[106:107], v108, off sc1
	v_add_f32_e32 v106, 1.0, v132
	v_mul_f32_e32 v110, v133, v106
	v_add_u32_e32 v106, v188, v48
	s_waitcnt vmcnt(24)
	v_fmac_f32_e32 v62, v34, v194
	s_waitcnt vmcnt(17)
	v_fmac_f32_e32 v61, v35, v194
	v_fmac_f32_e32 v60, v36, v194
	v_fmac_f32_e32 v59, v37, v194
	v_fmac_f32_e32 v58, v38, v194
	v_fmac_f32_e32 v57, v39, v194
	v_fmac_f32_e32 v56, v40, v194
	v_fmac_f32_e32 v55, v41, v194
	s_waitcnt vmcnt(16)
	v_fmac_f32_e32 v54, v42, v194
	s_waitcnt vmcnt(15)
	v_fmac_f32_e32 v53, v43, v194
	s_waitcnt vmcnt(14)
	v_fmac_f32_e32 v52, v44, v194
	s_waitcnt vmcnt(13)
	v_fmac_f32_e32 v51, v45, v194
	s_waitcnt vmcnt(12)
	v_fmac_f32_e32 v50, v46, v194
	s_waitcnt vmcnt(11)
	v_fmac_f32_e32 v49, v47, v194
	v_ashrrev_i32_e32 v107, 31, v106
	global_store_dword v[104:105], v196, off offset:128 sc1
	v_mul_f32_e32 v32, v110, v196
	global_store_dword v[84:85], v62, off offset:128 sc1
	global_store_dword v[82:83], v61, off offset:128 sc1
	global_store_dword v[78:79], v60, off offset:128 sc1
	global_store_dword v[72:73], v59, off offset:128 sc1
	global_store_dword v[74:75], v58, off offset:128 sc1
	global_store_dword v[76:77], v57, off offset:128 sc1
	global_store_dword v[80:81], v56, off offset:128 sc1
	global_store_dword v[86:87], v55, off offset:128 sc1
	global_store_dword v[90:91], v54, off offset:128 sc1
	global_store_dword v[92:93], v53, off offset:128 sc1
	global_store_dword v[94:95], v52, off offset:128 sc1
	global_store_dword v[96:97], v51, off offset:128 sc1
	global_store_dword v[98:99], v50, off offset:128 sc1
	global_store_dword v[100:101], v49, off offset:128 sc1
	v_cvt_pk_bf16_f32 v32, v32, s0
	v_lshl_add_u64 v[106:107], v[106:107], 1, s[8:9]
	v_add_u32_e32 v108, v186, v48
	global_load_dword v45, v[88:89], off offset:256
	v_ashrrev_i32_e32 v109, 31, v108
	global_store_short v[106:107], v32, off sc1
	v_mul_f32_e32 v113, v110, v56
	v_cvt_pk_bf16_f32 v113, v113, s0
	v_mul_f32_e32 v106, v196, v196
	s_waitcnt vmcnt(26)
	v_fmac_f32_e32 v63, v33, v194
	v_mul_f32_e32 v32, v110, v63
	v_cvt_pk_bf16_f32 v34, v32, s0
	v_lshl_add_u64 v[32:33], v[108:109], 1, s[8:9]
	global_store_short v[32:33], v34, off sc1
	v_add_u32_e32 v32, v184, v48
	v_ashrrev_i32_e32 v33, 31, v32
	v_mul_f32_e32 v34, v110, v62
	v_cvt_pk_bf16_f32 v34, v34, s0
	v_lshl_add_u64 v[32:33], v[32:33], 1, s[8:9]
	global_store_short v[32:33], v34, off sc1
	v_add_u32_e32 v32, v183, v48
	v_ashrrev_i32_e32 v33, 31, v32
	v_mul_f32_e32 v34, v110, v61
	v_cvt_pk_bf16_f32 v34, v34, s0
	v_lshl_add_u64 v[32:33], v[32:33], 1, s[8:9]
	global_store_short v[32:33], v34, off sc1
	v_add_u32_e32 v32, v181, v48
	v_ashrrev_i32_e32 v33, 31, v32
	v_mul_f32_e32 v34, v110, v60
	v_cvt_pk_bf16_f32 v34, v34, s0
	v_lshl_add_u64 v[32:33], v[32:33], 1, s[8:9]
	global_store_short v[32:33], v34, off sc1
	v_add_u32_e32 v32, v179, v48
	v_ashrrev_i32_e32 v33, 31, v32
	v_mul_f32_e32 v34, v110, v59
	v_cvt_pk_bf16_f32 v42, v34, s0
	v_lshl_add_u64 v[34:35], v[32:33], 1, s[8:9]
	v_or_b32_e32 v32, 64, v102
	v_ashrrev_i32_e32 v33, 31, v32
	v_lshlrev_b64 v[36:37], 2, v[32:33]
	global_store_dword v[88:89], v63, off offset:128 sc1
	v_lshl_add_u64 v[40:41], s[64:65], 0, v[36:37]
	v_lshl_add_u64 v[38:39], s[60:61], 0, v[36:37]
	global_load_dword v107, v[40:41], off
	global_load_dword v111, v[38:39], off
	v_mul_f32_e32 v33, v110, v58
	global_store_short v[34:35], v42, off sc1
	v_lshl_add_u64 v[34:35], s[62:63], 0, v[36:37]
	global_load_dword v112, v[34:35], off
	v_add_u32_e32 v34, v71, v48
	v_ashrrev_i32_e32 v35, 31, v34
	v_cvt_pk_bf16_f32 v33, v33, s0
	v_lshl_add_u64 v[34:35], v[34:35], 1, s[8:9]
	global_store_short v[34:35], v33, off sc1
	v_add_u32_e32 v34, v180, v48
	v_ashrrev_i32_e32 v35, 31, v34
	v_mul_f32_e32 v33, v110, v57
	v_cvt_pk_bf16_f32 v33, v33, s0
	v_lshl_add_u64 v[34:35], v[34:35], 1, s[8:9]
	global_load_dword v38, v[90:91], off offset:256
	global_load_dword v37, v[92:93], off offset:256
	global_load_dword v36, v[94:95], off offset:256
	global_load_dword v114, v[104:105], off offset:256
	global_load_dword v47, v[84:85], off offset:256
	global_load_dword v39, v[86:87], off offset:256
	global_load_dword v46, v[82:83], off offset:256
	global_load_dword v44, v[78:79], off offset:256
	global_load_dword v43, v[72:73], off offset:256
	global_load_dword v42, v[74:75], off offset:256
	global_load_dword v40, v[80:81], off offset:256
	global_load_dword v41, v[76:77], off offset:256
	v_add_u32_e32 v108, v182, v48
	global_store_short v[34:35], v33, off sc1
	global_load_dword v35, v[96:97], off offset:256
	v_ashrrev_i32_e32 v109, 31, v108
	global_load_dword v34, v[98:99], off offset:256
	global_load_dword v33, v[100:101], off offset:256
	v_lshl_add_u64 v[108:109], v[108:109], 1, s[8:9]
	global_store_short v[108:109], v113, off sc1
	v_add_u32_e32 v108, v185, v48
	v_ashrrev_i32_e32 v109, 31, v108
	v_mul_f32_e32 v113, v110, v55
	v_cvt_pk_bf16_f32 v113, v113, s0
	v_lshl_add_u64 v[108:109], v[108:109], 1, s[8:9]
	global_store_short v[108:109], v113, off sc1
	v_add_u32_e32 v108, v187, v48
	v_ashrrev_i32_e32 v109, 31, v108
	v_mul_f32_e32 v113, v110, v54
	v_cvt_pk_bf16_f32 v113, v113, s0
	v_lshl_add_u64 v[108:109], v[108:109], 1, s[8:9]
	global_store_short v[108:109], v113, off sc1
	v_add_u32_e32 v108, v189, v48
	v_ashrrev_i32_e32 v109, 31, v108
	v_mul_f32_e32 v113, v110, v53
	v_cvt_pk_bf16_f32 v113, v113, s0
	v_lshl_add_u64 v[108:109], v[108:109], 1, s[8:9]
	global_store_short v[108:109], v113, off sc1
	v_add_u32_e32 v108, v190, v48
	v_ashrrev_i32_e32 v109, 31, v108
	v_mul_f32_e32 v113, v110, v52
	v_cvt_pk_bf16_f32 v113, v113, s0
	v_lshl_add_u64 v[108:109], v[108:109], 1, s[8:9]
	global_store_short v[108:109], v113, off sc1
	v_add_u32_e32 v108, v191, v48
	v_ashrrev_i32_e32 v109, 31, v108
	v_mul_f32_e32 v113, v110, v51
	v_cvt_pk_bf16_f32 v113, v113, s0
	v_lshl_add_u64 v[108:109], v[108:109], 1, s[8:9]
	global_store_short v[108:109], v113, off sc1
	v_add_u32_e32 v108, v192, v48
	v_ashrrev_i32_e32 v109, 31, v108
	v_mul_f32_e32 v113, v110, v50
	v_cvt_pk_bf16_f32 v113, v113, s0
	v_lshl_add_u64 v[108:109], v[108:109], 1, s[8:9]
	global_store_short v[108:109], v113, off sc1
	v_add_u32_e32 v108, v193, v48
	v_ashrrev_i32_e32 v109, 31, v108
	v_mul_f32_e32 v48, v110, v49
	v_cvt_pk_bf16_f32 v48, v48, s0
	v_lshl_add_u64 v[108:109], v[108:109], 1, s[8:9]
	global_store_short v[108:109], v48, off sc1
	v_add_u32_e32 v108, v188, v32
	v_ashrrev_i32_e32 v109, 31, v108
	s_waitcnt vmcnt(28)
	v_add_f32_e32 v48, 1.0, v107
	s_waitcnt vmcnt(27)
	v_mul_f32_e32 v48, v111, v48
	v_fmac_f32_e32 v106, v197, v197
	s_waitcnt vmcnt(25)
	v_fmac_f32_e32 v45, v17, v112
	global_store_dword v[88:89], v45, off offset:256 sc1
	s_waitcnt vmcnt(24)
	v_fmac_f32_e32 v38, v26, v112
	s_waitcnt vmcnt(23)
	v_fmac_f32_e32 v37, v27, v112
	s_waitcnt vmcnt(22)
	v_fmac_f32_e32 v36, v28, v112
	s_waitcnt vmcnt(21)
	v_fmac_f32_e32 v114, v16, v112
	v_mul_f32_e32 v16, v48, v114
	s_waitcnt vmcnt(20)
	v_fmac_f32_e32 v47, v18, v112
	v_cvt_pk_bf16_f32 v18, v16, s0
	v_lshl_add_u64 v[16:17], v[108:109], 1, s[8:9]
	global_store_short v[16:17], v18, off sc1
	v_add_u32_e32 v16, v186, v32
	v_ashrrev_i32_e32 v17, 31, v16
	v_mul_f32_e32 v18, v48, v45
	v_cvt_pk_bf16_f32 v18, v18, s0
	v_lshl_add_u64 v[16:17], v[16:17], 1, s[8:9]
	global_store_short v[16:17], v18, off sc1
	v_add_u32_e32 v16, v184, v32
	v_ashrrev_i32_e32 v17, 31, v16
	v_mul_f32_e32 v18, v48, v47
	v_cvt_pk_bf16_f32 v18, v18, s0
	v_lshl_add_u64 v[16:17], v[16:17], 1, s[8:9]
	s_waitcnt vmcnt(20)
	v_fmac_f32_e32 v46, v19, v112
	global_store_short v[16:17], v18, off sc1
	v_add_u32_e32 v16, v183, v32
	v_ashrrev_i32_e32 v17, 31, v16
	v_mul_f32_e32 v18, v48, v46
	s_waitcnt vmcnt(20)
	v_fmac_f32_e32 v44, v20, v112
	v_cvt_pk_bf16_f32 v18, v18, s0
	v_lshl_add_u64 v[16:17], v[16:17], 1, s[8:9]
	global_store_short v[16:17], v18, off sc1
	v_mul_f32_e32 v16, v48, v44
	v_cvt_pk_bf16_f32 v26, v16, s0
	v_or_b32_e32 v16, 0x60, v102
	v_add_u32_e32 v18, v181, v32
	v_ashrrev_i32_e32 v17, 31, v16
	s_waitcnt vmcnt(20)
	v_fmac_f32_e32 v43, v21, v112
	s_waitcnt vmcnt(19)
	v_fmac_f32_e32 v42, v22, v112
	s_waitcnt vmcnt(17)
	v_fmac_f32_e32 v41, v23, v112
	v_fmac_f32_e32 v40, v24, v112
	v_fmac_f32_e32 v39, v25, v112
	s_waitcnt vmcnt(15)
	v_fmac_f32_e32 v35, v29, v112
	s_waitcnt vmcnt(14)
	v_fmac_f32_e32 v34, v30, v112
	s_waitcnt vmcnt(13)
	v_fmac_f32_e32 v33, v31, v112
	v_ashrrev_i32_e32 v19, 31, v18
	v_lshlrev_b64 v[20:21], 2, v[16:17]
	global_store_dword v[84:85], v47, off offset:256 sc1
	global_store_dword v[82:83], v46, off offset:256 sc1
	global_store_dword v[78:79], v44, off offset:256 sc1
	global_store_dword v[72:73], v43, off offset:256 sc1
	global_store_dword v[74:75], v42, off offset:256 sc1
	global_store_dword v[76:77], v41, off offset:256 sc1
	global_store_dword v[80:81], v40, off offset:256 sc1
	global_store_dword v[86:87], v39, off offset:256 sc1
	global_store_dword v[90:91], v38, off offset:256 sc1
	global_store_dword v[92:93], v37, off offset:256 sc1
	global_store_dword v[94:95], v36, off offset:256 sc1
	global_store_dword v[96:97], v35, off offset:256 sc1
	global_store_dword v[98:99], v34, off offset:256 sc1
	global_store_dword v[100:101], v33, off offset:256 sc1
	global_store_dword v[104:105], v114, off offset:256 sc1
	v_lshl_add_u64 v[24:25], s[64:65], 0, v[20:21]
	v_lshl_add_u64 v[18:19], v[18:19], 1, s[8:9]
	global_load_dword v29, v[104:105], off offset:384
	v_lshl_add_u64 v[22:23], s[60:61], 0, v[20:21]
	global_load_dword v17, v[24:25], off
	global_load_dword v30, v[22:23], off
	global_load_dword v28, v[88:89], off offset:384
	global_load_dword v27, v[84:85], off offset:384
	v_fmac_f32_e32 v106, v114, v114
	global_store_short v[18:19], v26, off sc1
	v_lshl_add_u64 v[18:19], s[62:63], 0, v[20:21]
	global_load_dword v102, v[18:19], off
	v_add_u32_e32 v18, v179, v32
	v_ashrrev_i32_e32 v19, 31, v18
	v_mul_f32_e32 v20, v48, v43
	v_cvt_pk_bf16_f32 v20, v20, s0
	v_lshl_add_u64 v[18:19], v[18:19], 1, s[8:9]
	global_store_short v[18:19], v20, off sc1
	v_add_u32_e32 v18, v71, v32
	v_ashrrev_i32_e32 v19, 31, v18
	v_mul_f32_e32 v20, v48, v42
	v_cvt_pk_bf16_f32 v20, v20, s0
	v_lshl_add_u64 v[18:19], v[18:19], 1, s[8:9]
	global_store_short v[18:19], v20, off sc1
	v_add_u32_e32 v18, v180, v32
	v_ashrrev_i32_e32 v19, 31, v18
	v_mul_f32_e32 v20, v48, v41
	v_cvt_pk_bf16_f32 v20, v20, s0
	v_lshl_add_u64 v[18:19], v[18:19], 1, s[8:9]
	global_store_short v[18:19], v20, off sc1
	v_add_u32_e32 v18, v182, v32
	v_ashrrev_i32_e32 v19, 31, v18
	v_mul_f32_e32 v20, v48, v40
	v_cvt_pk_bf16_f32 v20, v20, s0
	v_lshl_add_u64 v[18:19], v[18:19], 1, s[8:9]
	global_store_short v[18:19], v20, off sc1
	v_add_u32_e32 v18, v185, v32
	v_ashrrev_i32_e32 v19, 31, v18
	v_mul_f32_e32 v20, v48, v39
	v_cvt_pk_bf16_f32 v20, v20, s0
	v_lshl_add_u64 v[18:19], v[18:19], 1, s[8:9]
	global_store_short v[18:19], v20, off sc1
	v_add_u32_e32 v18, v187, v32
	v_ashrrev_i32_e32 v19, 31, v18
	v_mul_f32_e32 v20, v48, v38
	v_cvt_pk_bf16_f32 v20, v20, s0
	v_lshl_add_u64 v[18:19], v[18:19], 1, s[8:9]
	global_store_short v[18:19], v20, off sc1
	v_add_u32_e32 v18, v189, v32
	v_ashrrev_i32_e32 v19, 31, v18
	v_mul_f32_e32 v20, v48, v37
	v_cvt_pk_bf16_f32 v20, v20, s0
	v_lshl_add_u64 v[18:19], v[18:19], 1, s[8:9]
	global_store_short v[18:19], v20, off sc1
	v_add_u32_e32 v18, v190, v32
	v_ashrrev_i32_e32 v19, 31, v18
	v_mul_f32_e32 v20, v48, v36
	v_cvt_pk_bf16_f32 v20, v20, s0
	v_lshl_add_u64 v[18:19], v[18:19], 1, s[8:9]
	global_store_short v[18:19], v20, off sc1
	v_add_u32_e32 v18, v191, v32
	v_ashrrev_i32_e32 v19, 31, v18
	v_mul_f32_e32 v20, v48, v35
	v_cvt_pk_bf16_f32 v20, v20, s0
	v_lshl_add_u64 v[18:19], v[18:19], 1, s[8:9]
	global_store_short v[18:19], v20, off sc1
	v_add_u32_e32 v18, v192, v32
	v_ashrrev_i32_e32 v19, 31, v18
	v_mul_f32_e32 v20, v48, v34
	v_cvt_pk_bf16_f32 v20, v20, s0
	v_lshl_add_u64 v[18:19], v[18:19], 1, s[8:9]
	global_store_short v[18:19], v20, off sc1
	v_add_u32_e32 v18, v193, v32
	v_ashrrev_i32_e32 v19, 31, v18
	v_mul_f32_e32 v20, v48, v33
	v_cvt_pk_bf16_f32 v20, v20, s0
	v_lshl_add_u64 v[18:19], v[18:19], 1, s[8:9]
	global_store_short v[18:19], v20, off sc1
	global_load_dword v20, v[86:87], off offset:384
	v_add_u32_e32 v18, v188, v16
	global_load_dword v26, v[82:83], off offset:384
	global_load_dword v25, v[78:79], off offset:384
	global_load_dword v24, v[72:73], off offset:384
	global_load_dword v23, v[74:75], off offset:384
	global_load_dword v21, v[80:81], off offset:384
	global_load_dword v22, v[76:77], off offset:384
	s_waitcnt vmcnt(23)
	v_add_f32_e32 v17, 1.0, v17
	s_waitcnt vmcnt(22)
	v_mul_f32_e32 v32, v30, v17
	v_ashrrev_i32_e32 v19, 31, v18
	v_lshl_add_u64 v[18:19], v[18:19], 1, s[8:9]
	v_add_u32_e32 v30, v186, v16
	s_waitcnt vmcnt(18)
	v_fmac_f32_e32 v29, v0, v102
	v_mul_f32_e32 v0, v32, v29
	v_cvt_pk_bf16_f32 v0, v0, s0
	global_store_short v[18:19], v0, off sc1
	global_load_dword v19, v[90:91], off offset:384
	v_ashrrev_i32_e32 v31, 31, v30
	global_load_dword v18, v[92:93], off offset:384
	v_fmac_f32_e32 v28, v1, v102
	v_mul_f32_e32 v0, v32, v28
	v_cvt_pk_bf16_f32 v17, v0, s0
	v_lshl_add_u64 v[0:1], v[30:31], 1, s[8:9]
	global_store_short v[0:1], v17, off sc1
	v_add_u32_e32 v0, v184, v16
	v_fmac_f32_e32 v27, v2, v102
	global_load_dword v17, v[94:95], off offset:384
	v_ashrrev_i32_e32 v1, 31, v0
	v_mul_f32_e32 v2, v32, v27
	v_cvt_pk_bf16_f32 v2, v2, s0
	v_lshl_add_u64 v[0:1], v[0:1], 1, s[8:9]
	global_store_short v[0:1], v2, off sc1
	v_add_u32_e32 v0, v183, v16
	global_load_dword v2, v[96:97], off offset:384
	v_ashrrev_i32_e32 v1, 31, v0
	v_lshl_add_u64 v[0:1], v[0:1], 1, s[8:9]
	v_add_u32_e32 v30, v181, v16
	v_ashrrev_i32_e32 v31, 31, v30
	v_lshl_add_u64 v[30:31], v[30:31], 1, s[8:9]
	v_fmac_f32_e32 v106, v29, v29
	global_store_dword v[104:105], v29, off offset:384 sc1
	global_store_dword v[88:89], v28, off offset:384 sc1
	global_store_dword v[84:85], v27, off offset:384 sc1
	s_waitcnt vmcnt(16)
	v_fmac_f32_e32 v20, v9, v102
	global_store_dword v[86:87], v20, off offset:384 sc1
	s_waitcnt vmcnt(16)
	v_fmac_f32_e32 v26, v3, v102
	v_mul_f32_e32 v3, v32, v26
	v_cvt_pk_bf16_f32 v3, v3, s0
	global_store_short v[0:1], v3, off sc1
	global_load_dword v1, v[98:99], off offset:384
	s_waitcnt vmcnt(17)
	v_fmac_f32_e32 v25, v4, v102
	v_mul_f32_e32 v0, v32, v25
	v_cvt_pk_bf16_f32 v0, v0, s0
	global_store_short v[30:31], v0, off sc1
	global_load_dword v0, v[100:101], off offset:384
	v_add_u32_e32 v30, v179, v16
	s_waitcnt vmcnt(18)
	v_fmac_f32_e32 v24, v5, v102
	v_ashrrev_i32_e32 v31, 31, v30
	v_mul_f32_e32 v3, v32, v24
	v_cvt_pk_bf16_f32 v3, v3, s0
	v_lshl_add_u64 v[4:5], v[30:31], 1, s[8:9]
	global_store_short v[4:5], v3, off sc1
	v_add_u32_e32 v4, v71, v16
	s_waitcnt vmcnt(18)
	v_fmac_f32_e32 v23, v6, v102
	v_ashrrev_i32_e32 v5, 31, v4
	v_mul_f32_e32 v3, v32, v23
	v_cvt_pk_bf16_f32 v3, v3, s0
	v_lshl_add_u64 v[4:5], v[4:5], 1, s[8:9]
	global_store_short v[4:5], v3, off sc1
	v_add_u32_e32 v4, v180, v16
	s_waitcnt vmcnt(17)
	v_fmac_f32_e32 v22, v7, v102
	v_ashrrev_i32_e32 v5, 31, v4
	v_mul_f32_e32 v3, v32, v22
	v_cvt_pk_bf16_f32 v3, v3, s0
	v_lshl_add_u64 v[4:5], v[4:5], 1, s[8:9]
	global_store_short v[4:5], v3, off sc1
	v_add_u32_e32 v4, v182, v16
	v_fmac_f32_e32 v21, v8, v102
	v_ashrrev_i32_e32 v5, 31, v4
	v_mul_f32_e32 v3, v32, v21
	v_cvt_pk_bf16_f32 v3, v3, s0
	v_lshl_add_u64 v[4:5], v[4:5], 1, s[8:9]
	global_store_short v[4:5], v3, off sc1
	v_add_u32_e32 v4, v185, v16
	v_ashrrev_i32_e32 v5, 31, v4
	v_mul_f32_e32 v3, v32, v20
	v_cvt_pk_bf16_f32 v3, v3, s0
	v_lshl_add_u64 v[4:5], v[4:5], 1, s[8:9]
	global_store_short v[4:5], v3, off sc1
	v_add_u32_e32 v4, v187, v16
	s_waitcnt vmcnt(18)
	v_fmac_f32_e32 v19, v10, v102
	v_ashrrev_i32_e32 v5, 31, v4
	v_mul_f32_e32 v3, v32, v19
	v_cvt_pk_bf16_f32 v3, v3, s0
	v_lshl_add_u64 v[4:5], v[4:5], 1, s[8:9]
	global_store_short v[4:5], v3, off sc1
	v_add_u32_e32 v4, v189, v16
	s_waitcnt vmcnt(18)
	v_fmac_f32_e32 v18, v11, v102
	v_ashrrev_i32_e32 v5, 31, v4
	v_mul_f32_e32 v3, v32, v18
	v_cvt_pk_bf16_f32 v3, v3, s0
	v_lshl_add_u64 v[4:5], v[4:5], 1, s[8:9]
	global_store_short v[4:5], v3, off sc1
	v_add_u32_e32 v4, v190, v16
	s_waitcnt vmcnt(17)
	v_fmac_f32_e32 v17, v12, v102
	v_ashrrev_i32_e32 v5, 31, v4
	v_mul_f32_e32 v3, v32, v17
	v_cvt_pk_bf16_f32 v3, v3, s0
	v_lshl_add_u64 v[4:5], v[4:5], 1, s[8:9]
	global_store_short v[4:5], v3, off sc1
	v_add_u32_e32 v4, v191, v16
	s_waitcnt vmcnt(16)
	v_fmac_f32_e32 v2, v13, v102
	v_ashrrev_i32_e32 v5, 31, v4
	v_mul_f32_e32 v3, v32, v2
	v_cvt_pk_bf16_f32 v3, v3, s0
	v_lshl_add_u64 v[4:5], v[4:5], 1, s[8:9]
	global_store_short v[4:5], v3, off sc1
	v_add_u32_e32 v4, v192, v16
	v_ashrrev_i32_e32 v5, 31, v4
	v_lshl_add_u64 v[4:5], v[4:5], 1, s[8:9]
	v_xor_b32_e32 v13, 16, v164
	v_add_u32_e32 v10, v193, v16
	v_ashrrev_i32_e32 v11, 31, v10
	v_lshl_add_u64 v[10:11], v[10:11], 1, s[8:9]
	v_ashrrev_i32_e32 v71, 31, v70
	global_store_dword v[82:83], v26, off offset:384 sc1
	global_store_dword v[78:79], v25, off offset:384 sc1
	global_store_dword v[72:73], v24, off offset:384 sc1
	global_store_dword v[74:75], v23, off offset:384 sc1
	s_waitcnt vmcnt(15)
	v_fmac_f32_e32 v1, v14, v102
	v_mul_f32_e32 v3, v32, v1
	v_cvt_pk_bf16_f32 v3, v3, s0
	global_store_short v[4:5], v3, off sc1
	v_and_b32_e32 v4, 64, v164
	v_xor_b32_e32 v3, 1, v164
	v_add_u32_e32 v7, 64, v4
	v_cmp_lt_i32_e32 vcc, v3, v7
	v_xor_b32_e32 v4, 2, v164
	s_waitcnt vmcnt(14)
	v_fmac_f32_e32 v0, v15, v102
	v_cndmask_b32_e32 v3, v164, v3, vcc
	v_lshlrev_b32_e32 v3, 2, v3
	ds_bpermute_b32 v5, v3, v106
	v_cmp_lt_i32_e32 vcc, v4, v7
	v_mul_f32_e32 v12, v32, v0
	v_cvt_pk_bf16_f32 v12, v12, s0
	v_cndmask_b32_e32 v4, v164, v4, vcc
	v_lshlrev_b32_e32 v4, 2, v4
	s_waitcnt lgkmcnt(0)
	v_add_f32_e32 v6, v106, v5
	ds_bpermute_b32 v8, v4, v6
	v_xor_b32_e32 v5, 4, v164
	v_cmp_lt_i32_e32 vcc, v5, v7
	global_store_dword v[76:77], v22, off offset:384 sc1
	global_store_dword v[80:81], v21, off offset:384 sc1
	v_cndmask_b32_e32 v5, v164, v5, vcc
	v_lshlrev_b32_e32 v5, 2, v5
	s_waitcnt lgkmcnt(0)
	v_add_f32_e32 v8, v6, v8
	ds_bpermute_b32 v9, v5, v8
	v_xor_b32_e32 v6, 8, v164
	v_cmp_lt_i32_e32 vcc, v6, v7
	global_store_dword v[90:91], v19, off offset:384 sc1
	global_store_dword v[92:93], v18, off offset:384 sc1
	v_cndmask_b32_e32 v6, v164, v6, vcc
	v_lshlrev_b32_e32 v6, 2, v6
	s_waitcnt lgkmcnt(0)
	v_add_f32_e32 v8, v8, v9
	ds_bpermute_b32 v9, v6, v8
	v_cmp_lt_i32_e32 vcc, v13, v7
	global_store_dword v[94:95], v17, off offset:384 sc1
	global_store_dword v[96:97], v2, off offset:384 sc1
	v_cndmask_b32_e32 v7, v164, v13, vcc
	v_lshlrev_b32_e32 v7, 2, v7
	s_waitcnt lgkmcnt(0)
	v_add_f32_e32 v8, v8, v9
	ds_bpermute_b32 v9, v7, v8
	global_store_dword v[98:99], v1, off offset:384 sc1
	global_store_dword v[100:101], v0, off offset:384 sc1
	global_store_short v[10:11], v12, off sc1
	s_and_saveexec_b64 s[60:61], s[0:1]
	s_cbranch_execz .LBB0_1571
	s_waitcnt lgkmcnt(0)
	v_add_f32_e32 v10, v8, v9
	v_lshl_add_u64 v[8:9], v[70:71], 2, s[58:59]
	global_store_dword v[8:9], v10, off sc1

.LBB0_1601:
	s_cmp_gt_i32 s17, 25
	s_cselect_b64 s[6:7], -1, 0
	s_and_b64 s[0:1], s[4:5], s[6:7]
	s_andn2_b64 vcc, exec, s[0:1]
	s_cbranch_vccnz .LBB0_1613
	s_waitcnt vmcnt(0)
	v_or_b32_e32 v0, v201, v200
	s_movk_i32 s0, 0x3ff
	v_and_or_b32 v0, v0, s0, v199
	v_cmp_eq_u32_e32 vcc, 0, v0
	s_waitcnt lgkmcnt(0)
	s_barrier
	s_and_saveexec_b64 s[0:1], vcc
	s_cbranch_execz .LBB0_1612
	s_add_u32 s4, s14, 0x5be8c00
	s_addc_u32 s5, s15, 0
	s_lshl_b32 s3, s2, 1
	v_mov_b32_e32 v0, s3
	v_mov_b32_e32 v1, 0x9319
	global_store_short v0, v1, s[4:5] sc1
	s_cmp_lg_u32 s2, 0
	s_cbranch_scc1 .Lgbar_wait_24
	s_lshr_b32 s3, s33, 3
	s_bfm_b64 s[8:9], s3, 0
	s_cmpk_gt_u32 s33, 0x1ff
	s_cselect_b64 s[8:9], -1, s[8:9]
	s_mov_b64 exec, -1
	v_mbcnt_lo_u32_b32 v229, -1, 0
	v_mbcnt_hi_u32_b32 v229, -1, v229
	v_lshlrev_b32_e32 v229, 4, v229
	s_mov_b32 s10, 0x93199319
	s_mov_b64 exec, s[8:9]

.LBB0_1613:
	s_cmp_lt_i32 s16, 26
	s_cselect_b64 s[0:1], -1, 0
	s_and_b64 s[4:5], s[0:1], s[6:7]
	s_andn2_b64 vcc, exec, s[4:5]
	s_cbranch_vccnz .LBB0_1621
	s_ashr_i32 s3, s2, 31
	s_and_b32 s3, s3, s33
	s_add_i32 s3, s3, s2
	s_cmpk_gt_i32 s3, 0x15ff
	s_cbranch_scc1 .LBB0_1621
	v_lshrrev_b32_e32 v0, 3, v199
	s_waitcnt lgkmcnt(0)
	v_lshrrev_b32_e32 v1, 5, v199
	v_bfe_u32 v4, v199, 1, 3
	v_lshlrev_b32_e32 v5, 4, v199
	v_bfe_u32 v2, v199, 5, 1
	v_xor_b32_e32 v6, v5, v199
	v_lshlrev_b32_e32 v7, 11, v0
	s_movk_i32 s4, 0x70
	v_bitop3_b32 v1, v1, v4, 1 bitop3:0x6c
	v_and_or_b32 v76, v6, s4, v7
	v_lshlrev_b32_e32 v7, 4, v1
	v_bitop3_b32 v1, v2, v4, 2 bitop3:0x36
	v_lshrrev_b32_e32 v3, 1, v199
	v_lshlrev_b32_e32 v9, 4, v1
	v_bitop3_b32 v1, v2, v4, 4 bitop3:0x36
	v_mov_b32_e32 v77, 0
	v_and_b32_e32 v3, 0x1e0, v3
	v_lshlrev_b32_e32 v10, 4, v1
	v_bitop3_b32 v1, v2, v4, 6 bitop3:0x36
	v_lshlrev_b32_e32 v2, 4, v1
	v_and_or_b32 v93, v0, 4, v3
	v_lshl_add_u64 v[0:1], s[14:15], 0, v[76:77]
	s_mov_b64 s[6:7], 0x679f000
	v_lshl_add_u64 v[78:79], v[0:1], 0, s[6:7]
	s_mov_b64 s[6:7], 0x3aa0000
	v_lshl_add_u64 v[80:81], v[0:1], 0, s[6:7]
	s_add_u32 s6, s14, 0x5fce000
	s_addc_u32 s7, s15, 0
	v_and_b32_e32 v92, 31, v199
	s_add_u32 s10, s14, 0x5c3d800
	v_or_b32_e32 v6, v3, v92
	s_addc_u32 s11, s15, 0
	v_lshl_add_u32 v6, v6, 7, 0
	v_lshl_add_u32 v8, v92, 7, 0
	s_add_u32 s8, s14, 0x879f000
	v_add_u32_e32 v94, 0, v5
	s_mov_b32 s5, 0
	s_addc_u32 s9, s15, 0
	v_add_u32_e32 v95, 0x4000, v94
	s_mov_b64 s[18:19], 0x10000
	v_add_u32_e32 v96, 0x1000, v94
	v_add_u32_e32 v97, 0x5000, v94
	s_mov_b64 s[20:21], 0x20000
	v_add_u32_e32 v98, 0x2000, v94
	v_add_u32_e32 v99, 0x6000, v94
	s_mov_b64 s[22:23], 0x30000
	v_add_u32_e32 v100, 0x3000, v94
	v_add_u32_e32 v101, 0x7000, v94
	s_mov_b64 s[24:25], 0x679f080
	s_mov_b64 s[26:27], 0x3aa0080
	v_add_u32_e32 v102, 0x8000, v94
	v_add_u32_e32 v103, 0xc000, v94
	s_mov_b64 s[28:29], 0x67af080
	v_add_u32_e32 v104, 0x9000, v94
	s_mov_b64 s[30:31], 0x3ab0080
	v_add_u32_e32 v105, 0xd000, v94
	s_mov_b64 s[34:35], 0x67bf080
	v_add_u32_e32 v106, 0xa000, v94
	s_mov_b64 s[36:37], 0x3ac0080
	v_add_u32_e32 v107, 0xe000, v94
	s_mov_b64 s[38:39], 0x67cf080
	v_add_u32_e32 v108, 0xb000, v94
	s_mov_b64 s[40:41], 0x3ad0080
	v_add_u32_e32 v109, 0xf000, v94
	v_add_u32_e32 v110, v6, v7
	v_add_u32_e32 v111, v8, v7
	s_waitcnt vmcnt(5)
	v_add_u32_e32 v112, v6, v9
	v_add_u32_e32 v113, v8, v9
	v_add_u32_e32 v114, v6, v10
	v_add_u32_e32 v115, v8, v10
	s_waitcnt vmcnt(4)
	v_add_u32_e32 v116, v6, v2
	v_add_u32_e32 v117, v8, v2
	s_mov_b64 s[42:43], 0x679f100
	s_mov_b64 s[44:45], 0x3aa0100
	s_mov_b64 s[46:47], 0x67af100
	s_mov_b64 s[48:49], 0x3ab0100
	s_mov_b64 s[50:51], 0x67bf100
	s_mov_b64 s[52:53], 0x3ac0100
	s_mov_b64 s[54:55], 0x67cf100
	s_mov_b64 s[56:57], 0x3ad0100
	s_movk_i32 s68, 0x1600
	s_mov_b32 s69, 0x10000
	s_mov_b32 s70, 0x20000
	s_mov_b32 s71, 0x30000
	s_mov_b32 s72, 0x40000
	s_mov_b32 s73, 0x50000
	s_mov_b32 s74, 0x60000
	s_mov_b32 s75, 0x70000
	v_mov_b32_e32 v118, 0x358637bd
	s_mov_b32 s39, 0
	s_branch .LBB0_1617

.Lmap_done_3:
	s_lshl_b32 s60, s4, 7
	s_lshl_b32 s58, s76, 7
	s_ashr_i32 s61, s60, 31
	s_ashr_i32 s59, s58, 31
	s_lshl_b64 s[62:63], s[60:61], 11
	s_lshl_b64 s[64:65], s[58:59], 11
	s_cmp_eq_u32 s39, 1
	s_cbranch_scc1 .Lgk_pfhead_p25
	s_lshl_b32 s38, s60, 11
	s_add_u32 s18, s14, s38
	s_addc_u32 s19, s15, 0
	s_add_u32 s18, s18, 0x679f000
	s_addc_u32 s19, s19, 0
	s_add_u32 s20, s18, 0x10000
	s_addc_u32 s21, s19, 0
	s_add_u32 s22, s20, 0x10000
	s_addc_u32 s23, s21, 0
	s_add_u32 s24, s22, 0x10000
	s_addc_u32 s25, s23, 0
	s_lshl_b32 s38, s58, 11
	s_add_u32 s26, s14, s38
	s_addc_u32 s27, s15, 0
	s_add_u32 s26, s26, 0x3aa0000
	s_addc_u32 s27, s27, 0
	s_add_u32 s28, s26, 0x10000
	s_addc_u32 s29, s27, 0
	s_add_u32 s30, s28, 0x10000
	s_addc_u32 s31, s29, 0
	s_add_u32 s34, s30, 0x10000
	s_addc_u32 s35, s31, 0
	v_readfirstlane_b32 s36, v94
	v_mov_b32_e32 v254, v76
	s_mov_b32 m0, s36
	s_nop 0
	global_load_lds_dwordx4 v254, s[18:19]
	s_add_u32 m0, m0, 0x1000
	s_nop 0
	global_load_lds_dwordx4 v254, s[20:21]
	s_add_u32 m0, m0, 0x1000
	s_nop 0
	global_load_lds_dwordx4 v254, s[22:23]
	s_add_u32 m0, m0, 0x1000
	s_nop 0
	global_load_lds_dwordx4 v254, s[24:25]
	s_add_u32 m0, m0, 0x1000
	s_nop 0
	global_load_lds_dwordx4 v254, s[26:27]
	s_add_u32 m0, m0, 0x1000
	s_nop 0
	global_load_lds_dwordx4 v254, s[28:29]
	s_add_u32 m0, m0, 0x1000
	s_nop 0
	global_load_lds_dwordx4 v254, s[30:31]
	s_add_u32 m0, m0, 0x1000
	s_nop 0
	global_load_lds_dwordx4 v254, s[34:35]
	v_add_u32_e32 v254, 0x80, v254
	s_add_u32 m0, s36, 0x8000
	s_nop 0
	global_load_lds_dwordx4 v254, s[18:19]
	s_add_u32 m0, m0, 0x1000
	s_nop 0
	global_load_lds_dwordx4 v254, s[20:21]
	s_add_u32 m0, m0, 0x1000
	s_nop 0
	global_load_lds_dwordx4 v254, s[22:23]
	s_add_u32 m0, m0, 0x1000
	s_nop 0
	global_load_lds_dwordx4 v254, s[24:25]
	s_add_u32 m0, m0, 0x1000
	s_nop 0
	global_load_lds_dwordx4 v254, s[26:27]
	s_add_u32 m0, m0, 0x1000
	s_nop 0
	global_load_lds_dwordx4 v254, s[28:29]
	s_add_u32 m0, m0, 0x1000
	s_nop 0
	global_load_lds_dwordx4 v254, s[30:31]
	s_add_u32 m0, m0, 0x1000
	s_nop 0
	global_load_lds_dwordx4 v254, s[34:35]
	v_add_u32_e32 v254, 0x80, v254

.Lmap_done_3_pf_p25:
	s_lshl_b32 s44, s41, 7
	s_lshl_b32 s42, s50, 7
	s_ashr_i32 s45, s44, 31
	s_ashr_i32 s43, s42, 31
	s_lshl_b64 s[46:47], s[44:45], 11
	s_lshl_b64 s[48:49], s[42:43], 11
	s_lshl_b32 s38, s44, 11
	s_add_u32 s18, s14, s38
	s_addc_u32 s19, s15, 0
	s_add_u32 s18, s18, 0x679f000
	s_addc_u32 s19, s19, 0
	s_add_u32 s20, s18, 0x10000
	s_addc_u32 s21, s19, 0
	s_add_u32 s22, s20, 0x10000
	s_addc_u32 s23, s21, 0
	s_add_u32 s24, s22, 0x10000
	s_addc_u32 s25, s23, 0
	s_lshl_b32 s38, s42, 11
	s_add_u32 s26, s14, s38
	s_addc_u32 s27, s15, 0
	s_add_u32 s26, s26, 0x3aa0000
	s_addc_u32 s27, s27, 0
	s_add_u32 s28, s26, 0x10000
	s_addc_u32 s29, s27, 0
	s_add_u32 s30, s28, 0x10000
	s_addc_u32 s31, s29, 0
	s_add_u32 s34, s30, 0x10000
	s_addc_u32 s35, s31, 0
	v_mov_b32_e32 v254, v76
	s_mov_b32 s39, 1
	s_waitcnt vmcnt(8)
	s_barrier
	ds_read_b128 v[64:67], v110
	ds_read_b128 v[68:71], v111 offset:16384
	ds_read_b128 v[72:75], v111 offset:20480
	ds_read_b128 v[82:85], v111 offset:24576
	ds_read_b128 v[86:89], v111 offset:28672
	ds_read_b128 v[120:123], v112
	ds_read_b128 v[124:127], v113 offset:16384
	ds_read_b128 v[128:131], v113 offset:20480
	ds_read_b128 v[132:135], v113 offset:24576
	ds_read_b128 v[136:139], v113 offset:28672
	ds_read_b128 v[140:143], v114
	ds_read_b128 v[218:221], v115 offset:16384
	ds_read_b128 v[222:225], v115 offset:20480
	ds_read_b128 v[226:229], v115 offset:24576
	ds_read_b128 v[230:233], v115 offset:28672
	ds_read_b128 v[234:237], v116
	ds_read_b128 v[238:241], v117 offset:16384
	ds_read_b128 v[242:245], v117 offset:20480
	ds_read_b128 v[246:249], v117 offset:24576
	ds_read_b128 v[250:253], v117 offset:28672
	s_waitcnt lgkmcnt(0)
	s_barrier
	s_mov_b32 m0, s36
	s_setprio 1
	v_mfma_f32_32x32x16_bf16 v[48:63], v[64:67], v[68:71], v[48:63]
	v_mfma_f32_32x32x16_bf16 v[32:47], v[64:67], v[72:75], v[32:47]
	global_load_lds_dwordx4 v254, s[18:19]
	s_add_u32 m0, m0, 0x1000
	v_mfma_f32_32x32x16_bf16 v[16:31], v[64:67], v[82:85], v[16:31]
	v_mfma_f32_32x32x16_bf16 v[0:15], v[64:67], v[86:89], v[0:15]
	global_load_lds_dwordx4 v254, s[20:21]
	s_add_u32 m0, m0, 0x1000
	v_mfma_f32_32x32x16_bf16 v[48:63], v[120:123], v[124:127], v[48:63]
	v_mfma_f32_32x32x16_bf16 v[32:47], v[120:123], v[128:131], v[32:47]
	global_load_lds_dwordx4 v254, s[22:23]
	s_add_u32 m0, m0, 0x1000
	v_mfma_f32_32x32x16_bf16 v[16:31], v[120:123], v[132:135], v[16:31]
	v_mfma_f32_32x32x16_bf16 v[0:15], v[120:123], v[136:139], v[0:15]
	global_load_lds_dwordx4 v254, s[24:25]
	s_add_u32 m0, m0, 0x1000
	v_mfma_f32_32x32x16_bf16 v[48:63], v[140:143], v[218:221], v[48:63]
	v_mfma_f32_32x32x16_bf16 v[32:47], v[140:143], v[222:225], v[32:47]
	global_load_lds_dwordx4 v254, s[26:27]
	s_add_u32 m0, m0, 0x1000
	v_mfma_f32_32x32x16_bf16 v[16:31], v[140:143], v[226:229], v[16:31]
	v_mfma_f32_32x32x16_bf16 v[0:15], v[140:143], v[230:233], v[0:15]
	global_load_lds_dwordx4 v254, s[28:29]
	s_add_u32 m0, m0, 0x1000
	v_mfma_f32_32x32x16_bf16 v[48:63], v[234:237], v[238:241], v[48:63]
	v_mfma_f32_32x32x16_bf16 v[32:47], v[234:237], v[242:245], v[32:47]
	global_load_lds_dwordx4 v254, s[30:31]
	s_add_u32 m0, m0, 0x1000
	v_mfma_f32_32x32x16_bf16 v[16:31], v[234:237], v[246:249], v[16:31]
	v_mfma_f32_32x32x16_bf16 v[0:15], v[234:237], v[250:253], v[0:15]
	global_load_lds_dwordx4 v254, s[34:35]
	s_setprio 0
	v_add_u32_e32 v254, 0x80, v254
	s_waitcnt vmcnt(8)
	s_barrier
	ds_read_b128 v[64:67], v110 offset:32768
	ds_read_b128 v[68:71], v111 offset:49152
	ds_read_b128 v[72:75], v111 offset:53248
	ds_read_b128 v[82:85], v111 offset:57344
	ds_read_b128 v[86:89], v111 offset:61440
	ds_read_b128 v[120:123], v112 offset:32768
	ds_read_b128 v[124:127], v113 offset:49152
	ds_read_b128 v[128:131], v113 offset:53248
	ds_read_b128 v[132:135], v113 offset:57344
	ds_read_b128 v[136:139], v113 offset:61440
	ds_read_b128 v[140:143], v114 offset:32768
	ds_read_b128 v[218:221], v115 offset:49152
	ds_read_b128 v[222:225], v115 offset:53248
	ds_read_b128 v[226:229], v115 offset:57344
	ds_read_b128 v[230:233], v115 offset:61440
	ds_read_b128 v[234:237], v116 offset:32768
	ds_read_b128 v[238:241], v117 offset:49152
	ds_read_b128 v[242:245], v117 offset:53248
	ds_read_b128 v[246:249], v117 offset:57344
	ds_read_b128 v[250:253], v117 offset:61440
	s_waitcnt lgkmcnt(0)
	s_barrier
	s_add_u32 m0, s36, 0x8000
	s_setprio 1
	v_mfma_f32_32x32x16_bf16 v[48:63], v[64:67], v[68:71], v[48:63]
	v_mfma_f32_32x32x16_bf16 v[32:47], v[64:67], v[72:75], v[32:47]
	global_load_lds_dwordx4 v254, s[18:19]
	s_add_u32 m0, m0, 0x1000
	v_mfma_f32_32x32x16_bf16 v[16:31], v[64:67], v[82:85], v[16:31]
	v_mfma_f32_32x32x16_bf16 v[0:15], v[64:67], v[86:89], v[0:15]
	global_load_lds_dwordx4 v254, s[20:21]
	s_add_u32 m0, m0, 0x1000
	v_mfma_f32_32x32x16_bf16 v[48:63], v[120:123], v[124:127], v[48:63]
	v_mfma_f32_32x32x16_bf16 v[32:47], v[120:123], v[128:131], v[32:47]
	global_load_lds_dwordx4 v254, s[22:23]
	s_add_u32 m0, m0, 0x1000
	v_mfma_f32_32x32x16_bf16 v[16:31], v[120:123], v[132:135], v[16:31]
	v_mfma_f32_32x32x16_bf16 v[0:15], v[120:123], v[136:139], v[0:15]
	global_load_lds_dwordx4 v254, s[24:25]
	s_add_u32 m0, m0, 0x1000
	v_mfma_f32_32x32x16_bf16 v[48:63], v[140:143], v[218:221], v[48:63]
	v_mfma_f32_32x32x16_bf16 v[32:47], v[140:143], v[222:225], v[32:47]
	global_load_lds_dwordx4 v254, s[26:27]
	s_add_u32 m0, m0, 0x1000
	v_mfma_f32_32x32x16_bf16 v[16:31], v[140:143], v[226:229], v[16:31]
	v_mfma_f32_32x32x16_bf16 v[0:15], v[140:143], v[230:233], v[0:15]
	global_load_lds_dwordx4 v254, s[28:29]
	s_add_u32 m0, m0, 0x1000
	v_mfma_f32_32x32x16_bf16 v[48:63], v[234:237], v[238:241], v[48:63]
	v_mfma_f32_32x32x16_bf16 v[32:47], v[234:237], v[242:245], v[32:47]
	global_load_lds_dwordx4 v254, s[30:31]
	s_add_u32 m0, m0, 0x1000
	v_mfma_f32_32x32x16_bf16 v[16:31], v[234:237], v[246:249], v[16:31]
	v_mfma_f32_32x32x16_bf16 v[0:15], v[234:237], v[250:253], v[0:15]
	global_load_lds_dwordx4 v254, s[34:35]
	s_setprio 0
	v_add_u32_e32 v254, 0x80, v254
	s_branch .LBB0_1616

.LBB0_1621:
	s_cmp_gt_i32 s17, 26
	s_cselect_b64 s[4:5], -1, 0
	s_and_b64 s[0:1], s[0:1], s[4:5]
	s_andn2_b64 vcc, exec, s[0:1]
	s_cbranch_vccnz .LBB0_1633
	s_waitcnt vmcnt(0)
	v_or_b32_e32 v0, v201, v200
	s_movk_i32 s0, 0x3ff
	v_and_or_b32 v0, v0, s0, v199
	v_cmp_eq_u32_e32 vcc, 0, v0
	s_waitcnt lgkmcnt(0)
	s_barrier
	s_and_saveexec_b64 s[0:1], vcc
	s_cbranch_execz .LBB0_1632
	s_add_u32 s6, s14, 0x5be8c00
	s_addc_u32 s7, s15, 0
	s_lshl_b32 s3, s2, 1
	v_mov_b32_e32 v0, s3
	v_mov_b32_e32 v1, 0x931a
	global_store_short v0, v1, s[6:7] sc1
	s_cmp_lg_u32 s2, 0
	s_cbranch_scc1 .Lgbar_wait_25
	s_lshr_b32 s3, s33, 3
	s_bfm_b64 s[8:9], s3, 0
	s_cmpk_gt_u32 s33, 0x1ff
	s_cselect_b64 s[8:9], -1, s[8:9]
	s_mov_b64 exec, -1
	v_mbcnt_lo_u32_b32 v229, -1, 0
	v_mbcnt_hi_u32_b32 v229, -1, v229
	v_lshlrev_b32_e32 v229, 4, v229
	s_mov_b32 s10, 0x931a931a
	s_mov_b64 exec, s[8:9]

.LBB0_1633:
	s_cmp_lt_i32 s16, 27
	s_cselect_b64 s[0:1], -1, 0
	s_and_b64 s[4:5], s[0:1], s[4:5]
	s_andn2_b64 vcc, exec, s[4:5]
	s_cbranch_vccnz .LBB0_1641
	s_ashr_i32 s3, s2, 31
	s_and_b32 s3, s3, s33
	s_add_i32 s10, s3, s2
	s_cmpk_gt_i32 s10, 0x3ff
	s_cbranch_scc1 .LBB0_1641
	s_waitcnt lgkmcnt(0)
	v_lshrrev_b32_e32 v1, 5, v199
	v_bfe_u32 v5, v199, 1, 3
	v_lshrrev_b32_e32 v6, 4, v199
	v_lshrrev_b32_e32 v0, 3, v199
	v_bfe_u32 v2, v199, 5, 1
	v_xor_b32_e32 v7, v6, v199
	v_bitop3_b32 v1, v1, v5, 1 bitop3:0x6c
	v_mul_u32_u24_e32 v3, 0xb00, v0
	v_lshlrev_b32_e32 v7, 3, v7
	v_lshlrev_b32_e32 v9, 4, v1
	v_bitop3_b32 v1, v2, v5, 2 bitop3:0x36
	v_lshrrev_b32_e32 v4, 1, v199
	v_and_or_b32 v7, v7, 56, v3
	v_lshlrev_b32_e32 v11, 4, v1
	v_bitop3_b32 v1, v2, v5, 4 bitop3:0x36
	v_lshlrev_b32_e32 v64, 1, v7
	v_mov_b32_e32 v65, 0
	v_and_b32_e32 v4, 0x1e0, v4
	v_lshlrev_b32_e32 v12, 4, v1
	v_bitop3_b32 v1, v2, v5, 6 bitop3:0x36
	v_and_b32_e32 v74, 31, v199
	v_lshlrev_b32_e32 v2, 4, v1
	v_and_or_b32 v75, v0, 4, v4
	v_lshl_add_u64 v[0:1], s[14:15], 0, v[64:65]
	s_mov_b64 s[4:5], 0x879f000
	v_lshlrev_b32_e32 v7, 4, v199
	v_or_b32_e32 v8, v4, v74
	v_lshl_add_u64 v[66:67], v[0:1], 0, s[4:5]
	s_mov_b64 s[4:5], 0x5620000
	v_lshl_add_u32 v8, v8, 7, 0
	v_lshl_add_u32 v10, v74, 7, 0
	v_lshl_add_u64 v[68:69], v[0:1], 0, s[4:5]
	v_bitop3_b32 v0, v6, 7, v199 bitop3:0x48
	v_lshlrev_b32_e32 v1, 1, v3
	v_add_u32_e32 v77, 0, v7
	s_mov_b32 s3, 0
	v_lshl_or_b32 v64, v0, 4, v1
	v_mov_b32_e32 v76, 0x1600
	v_add_u32_e32 v78, 0x4000, v77
	s_mov_b64 s[4:5], 0x2c000
	v_add_u32_e32 v79, 0x1000, v77
	v_add_u32_e32 v80, 0x5000, v77
	s_mov_b64 s[6:7], 0x58000
	v_add_u32_e32 v81, 0x2000, v77
	v_add_u32_e32 v82, 0x6000, v77
	s_mov_b64 s[8:9], 0x84000
	v_add_u32_e32 v83, 0x3000, v77
	v_add_u32_e32 v84, 0x7000, v77
	s_mov_b64 s[18:19], 0x879f080
	s_mov_b64 s[20:21], 0x5620080
	v_add_u32_e32 v85, 0x8000, v77
	v_add_u32_e32 v86, 0xc000, v77
	s_mov_b64 s[22:23], 0x87cb080
	v_add_u32_e32 v87, 0x9000, v77
	s_mov_b64 s[24:25], 0x564c080
	v_add_u32_e32 v88, 0xd000, v77
	s_mov_b64 s[26:27], 0x87f7080
	v_add_u32_e32 v89, 0xa000, v77
	s_mov_b64 s[28:29], 0x5678080
	v_add_u32_e32 v90, 0xe000, v77
	s_mov_b64 s[30:31], 0x8823080
	v_add_u32_e32 v91, 0xb000, v77
	s_mov_b64 s[34:35], 0x56a4080
	v_add_u32_e32 v92, 0xf000, v77
	v_add_u32_e32 v93, v8, v9
	v_add_u32_e32 v94, v10, v9
	v_add_u32_e32 v95, v8, v11
	v_add_u32_e32 v96, v10, v11
	v_add_u32_e32 v97, v8, v12
	v_add_u32_e32 v98, v10, v12
	v_add_u32_e32 v99, v8, v2
	v_add_u32_e32 v100, v10, v2
	s_mov_b64 s[36:37], 0x879f100
	s_mov_b64 s[38:39], 0x5620100
	s_mov_b64 s[40:41], 0x87cb100
	s_mov_b64 s[42:43], 0x564c100
	s_mov_b64 s[44:45], 0x87f7100
	s_mov_b64 s[46:47], 0x5678100
	s_mov_b64 s[48:49], 0x8823100
	s_mov_b64 s[50:51], 0x56a4100
	s_mov_b32 s39, 0
	s_branch .LBB0_1637
.LBB0_1636:
	s_add_i32 s52, s11, 0xffffe000
	s_lshr_b32 s52, s52, 12
	s_mulk_i32 s52, 0x1800
	s_add_i32 s52, s52, 0xf000
	s_cmp_gt_i32 s2, 63
	s_cselect_b32 s2, s52, 0xd800
	s_lshl_b64 s[52:53], s[2:3], 2
	s_add_u32 s2, s14, s52
	s_addc_u32 s53, s15, s53
	s_add_u32 s52, s2, 0x5ba5000
	v_or_b32_e32 v72, s16, v74
	s_addc_u32 s53, s53, 0
	v_ashrrev_i32_e32 v73, 31, v72
	v_lshl_add_u64 v[70:71], v[72:73], 2, s[52:53]
	global_load_dword v146, v[70:71], off
	v_add_lshl_u32 v71, s11, v75, 10
	v_or_b32_e32 v73, 0x400, v71
	v_add_u32_e32 v102, v73, v72
	v_ashrrev_i32_e32 v103, 31, v102
	v_or_b32_e32 v101, 0x800, v71
	v_lshl_add_u64 v[116:117], v[102:103], 2, s[12:13]
	v_add_u32_e32 v102, v101, v72
	v_ashrrev_i32_e32 v103, 31, v102
	v_lshl_add_u64 v[118:119], v[102:103], 2, s[12:13]
	v_or_b32_e32 v102, 0xc00, v71
	v_add_u32_e32 v104, v102, v72
	v_ashrrev_i32_e32 v105, 31, v104
	v_or_b32_e32 v103, 0x2000, v71
	v_lshl_add_u64 v[120:121], v[104:105], 2, s[12:13]
	v_add_u32_e32 v104, v103, v72
	v_ashrrev_i32_e32 v105, 31, v104
	v_lshl_add_u64 v[122:123], v[104:105], 2, s[12:13]
	v_or_b32_e32 v104, 0x2400, v71
	v_add_u32_e32 v106, v104, v72
	v_ashrrev_i32_e32 v107, 31, v106
	v_or_b32_e32 v105, 0x2800, v71
	v_lshl_add_u64 v[124:125], v[106:107], 2, s[12:13]
	v_add_u32_e32 v106, v105, v72
	v_ashrrev_i32_e32 v107, 31, v106
	v_lshl_add_u64 v[126:127], v[106:107], 2, s[12:13]
	v_or_b32_e32 v106, 0x2c00, v71
	v_add_u32_e32 v108, v106, v72
	v_ashrrev_i32_e32 v109, 31, v108
	v_or_b32_e32 v107, 0x4000, v71
	v_lshl_add_u64 v[128:129], v[108:109], 2, s[12:13]
	v_add_u32_e32 v108, v107, v72
	v_ashrrev_i32_e32 v109, 31, v108
	v_lshl_add_u64 v[130:131], v[108:109], 2, s[12:13]
	v_or_b32_e32 v108, 0x4400, v71
	v_add_u32_e32 v110, v108, v72
	v_ashrrev_i32_e32 v111, 31, v110
	v_or_b32_e32 v109, 0x4800, v71
	v_lshl_add_u64 v[132:133], v[110:111], 2, s[12:13]
	v_add_u32_e32 v110, v109, v72
	v_ashrrev_i32_e32 v111, 31, v110
	v_lshl_add_u64 v[134:135], v[110:111], 2, s[12:13]
	v_or_b32_e32 v110, 0x4c00, v71
	v_add_u32_e32 v112, v110, v72
	v_ashrrev_i32_e32 v113, 31, v112
	v_or_b32_e32 v111, 0x6000, v71
	v_lshl_add_u64 v[136:137], v[112:113], 2, s[12:13]
	v_add_u32_e32 v112, v111, v72
	v_ashrrev_i32_e32 v113, 31, v112
	v_lshl_add_u64 v[138:139], v[112:113], 2, s[12:13]
	v_or_b32_e32 v112, 0x6400, v71
	v_add_u32_e32 v114, v112, v72
	v_ashrrev_i32_e32 v115, 31, v114
	v_or_b32_e32 v113, 0x6800, v71
	v_lshl_add_u64 v[140:141], v[114:115], 2, s[12:13]
	v_add_u32_e32 v114, v113, v72
	v_ashrrev_i32_e32 v115, 31, v114
	v_lshl_add_u64 v[142:143], v[114:115], 2, s[12:13]
	v_or_b32_e32 v114, 0x6c00, v71
	v_add_u32_e32 v144, v114, v72
	v_ashrrev_i32_e32 v145, 31, v144
	v_add_u32_e32 v70, v71, v72
	v_lshl_add_u64 v[144:145], v[144:145], 2, s[12:13]
	global_load_dword v147, v[116:117], off
	global_load_dword v148, v[118:119], off
	global_load_dword v149, v[120:121], off
	global_load_dword v150, v[122:123], off
	global_load_dword v151, v[124:125], off
	global_load_dword v152, v[126:127], off
	global_load_dword v153, v[128:129], off
	global_load_dword v154, v[130:131], off
	global_load_dword v155, v[132:133], off
	global_load_dword v156, v[134:135], off
	global_load_dword v115, v[136:137], off
	global_load_dword v157, v[138:139], off
	global_load_dword v158, v[140:141], off
	global_load_dword v159, v[142:143], off
	global_load_dword v160, v[144:145], off
	v_ashrrev_i32_e32 v71, 31, v70
	v_lshl_add_u64 v[70:71], v[70:71], 2, s[12:13]
	global_load_dword v161, v[70:71], off
	s_add_i32 s10, s10, s33
	s_cmpk_gt_i32 s10, 0x3ff
	s_waitcnt vmcnt(0)
	v_fmac_f32_e32 v147, v49, v146
	v_fmac_f32_e32 v148, v50, v146
	v_fmac_f32_e32 v149, v51, v146
	v_fmac_f32_e32 v150, v52, v146
	v_fmac_f32_e32 v151, v53, v146
	v_fmac_f32_e32 v152, v54, v146
	v_fmac_f32_e32 v153, v55, v146
	v_fmac_f32_e32 v154, v56, v146
	v_fmac_f32_e32 v155, v57, v146
	v_fmac_f32_e32 v156, v58, v146
	v_fmac_f32_e32 v115, v59, v146
	v_fmac_f32_e32 v157, v60, v146
	v_fmac_f32_e32 v158, v61, v146
	v_fmac_f32_e32 v159, v62, v146
	v_fmac_f32_e32 v160, v63, v146
	global_store_dword v[116:117], v147, off sc1
	global_store_dword v[118:119], v148, off sc1
	global_store_dword v[120:121], v149, off sc1
	global_store_dword v[122:123], v150, off sc1
	global_store_dword v[124:125], v151, off sc1
	global_store_dword v[126:127], v152, off sc1
	global_store_dword v[128:129], v153, off sc1
	global_store_dword v[130:131], v154, off sc1
	global_store_dword v[132:133], v155, off sc1
	global_store_dword v[134:135], v156, off sc1
	global_store_dword v[136:137], v115, off sc1
	global_store_dword v[138:139], v157, off sc1
	global_store_dword v[140:141], v158, off sc1
	global_store_dword v[142:143], v159, off sc1
	global_store_dword v[144:145], v160, off sc1
	global_load_dword v115, v[70:71], off offset:128
	v_fmac_f32_e32 v161, v48, v146
	v_or_b32_e32 v48, 32, v72
	v_ashrrev_i32_e32 v49, 31, v48
	global_store_dword v[70:71], v161, off sc1
	v_lshl_add_u64 v[50:51], v[48:49], 2, s[52:53]
	global_load_dword v134, v[50:51], off
	v_add_u32_e32 v50, v73, v48
	v_add_u32_e32 v118, v108, v48
	v_add_u32_e32 v52, v101, v48
	v_add_u32_e32 v54, v102, v48
	v_add_u32_e32 v56, v103, v48
	v_add_u32_e32 v58, v104, v48
	v_add_u32_e32 v60, v105, v48
	v_add_u32_e32 v62, v106, v48
	v_add_u32_e32 v116, v107, v48
	v_add_u32_e32 v120, v109, v48
	v_add_u32_e32 v122, v110, v48
	v_add_u32_e32 v124, v111, v48
	v_add_u32_e32 v126, v112, v48
	v_ashrrev_i32_e32 v51, 31, v50
	v_ashrrev_i32_e32 v119, 31, v118
	v_add_u32_e32 v128, v113, v48
	v_add_u32_e32 v48, v114, v48
	v_ashrrev_i32_e32 v53, 31, v52
	v_ashrrev_i32_e32 v55, 31, v54
	v_ashrrev_i32_e32 v57, 31, v56
	v_ashrrev_i32_e32 v59, 31, v58
	v_ashrrev_i32_e32 v61, 31, v60
	v_ashrrev_i32_e32 v63, 31, v62
	v_ashrrev_i32_e32 v117, 31, v116
	v_ashrrev_i32_e32 v121, 31, v120
	v_ashrrev_i32_e32 v123, 31, v122
	v_ashrrev_i32_e32 v125, 31, v124
	v_lshl_add_u64 v[50:51], v[50:51], 2, s[12:13]
	v_lshl_add_u64 v[118:119], v[118:119], 2, s[12:13]
	v_ashrrev_i32_e32 v127, 31, v126
	v_ashrrev_i32_e32 v129, 31, v128
	v_ashrrev_i32_e32 v49, 31, v48
	v_lshl_add_u64 v[52:53], v[52:53], 2, s[12:13]
	v_lshl_add_u64 v[54:55], v[54:55], 2, s[12:13]
	v_lshl_add_u64 v[56:57], v[56:57], 2, s[12:13]
	v_lshl_add_u64 v[58:59], v[58:59], 2, s[12:13]
	v_lshl_add_u64 v[60:61], v[60:61], 2, s[12:13]
	v_lshl_add_u64 v[62:63], v[62:63], 2, s[12:13]
	v_lshl_add_u64 v[116:117], v[116:117], 2, s[12:13]
	v_lshl_add_u64 v[120:121], v[120:121], 2, s[12:13]
	v_lshl_add_u64 v[122:123], v[122:123], 2, s[12:13]
	v_lshl_add_u64 v[124:125], v[124:125], 2, s[12:13]
	v_lshl_add_u64 v[126:127], v[126:127], 2, s[12:13]
	v_lshl_add_u64 v[128:129], v[128:129], 2, s[12:13]
	v_lshl_add_u64 v[48:49], v[48:49], 2, s[12:13]
	v_or_b32_e32 v130, 64, v72
	v_ashrrev_i32_e32 v131, 31, v130
	v_lshl_add_u64 v[132:133], v[130:131], 2, s[52:53]
	s_waitcnt vmcnt(0)
	v_fmac_f32_e32 v115, v32, v134
	global_store_dword v[70:71], v115, off offset:128 sc1
	global_load_dword v32, v[50:51], off
	s_nop 0
	global_load_dword v115, v[52:53], off
	global_load_dword v135, v[54:55], off
	global_load_dword v136, v[56:57], off
	global_load_dword v137, v[58:59], off
	global_load_dword v138, v[60:61], off
	global_load_dword v139, v[62:63], off
	global_load_dword v140, v[116:117], off
	global_load_dword v141, v[118:119], off
	global_load_dword v142, v[120:121], off
	global_load_dword v143, v[122:123], off
	global_load_dword v144, v[124:125], off
	global_load_dword v145, v[126:127], off
	global_load_dword v146, v[128:129], off
	global_load_dword v147, v[48:49], off
	s_waitcnt vmcnt(14)
	v_fmac_f32_e32 v32, v33, v134
	s_waitcnt vmcnt(13)
	v_fmac_f32_e32 v115, v34, v134
	s_waitcnt vmcnt(12)
	v_fmac_f32_e32 v135, v35, v134
	s_waitcnt vmcnt(11)
	v_fmac_f32_e32 v136, v36, v134
	s_waitcnt vmcnt(10)
	v_fmac_f32_e32 v137, v37, v134
	s_waitcnt vmcnt(9)
	v_fmac_f32_e32 v138, v38, v134
	s_waitcnt vmcnt(8)
	v_fmac_f32_e32 v139, v39, v134
	s_waitcnt vmcnt(7)
	v_fmac_f32_e32 v140, v40, v134
	s_waitcnt vmcnt(6)
	v_fmac_f32_e32 v141, v41, v134
	s_waitcnt vmcnt(5)
	v_fmac_f32_e32 v142, v42, v134
	s_waitcnt vmcnt(4)
	v_fmac_f32_e32 v143, v43, v134
	s_waitcnt vmcnt(3)
	v_fmac_f32_e32 v144, v44, v134
	s_waitcnt vmcnt(2)
	v_fmac_f32_e32 v145, v45, v134
	s_waitcnt vmcnt(1)
	v_fmac_f32_e32 v146, v46, v134
	s_waitcnt vmcnt(0)
	v_fmac_f32_e32 v147, v47, v134
	global_store_dword v[50:51], v32, off sc1
	global_store_dword v[52:53], v115, off sc1
	global_store_dword v[54:55], v135, off sc1
	global_store_dword v[56:57], v136, off sc1
	global_store_dword v[58:59], v137, off sc1
	global_store_dword v[60:61], v138, off sc1
	global_store_dword v[62:63], v139, off sc1
	global_store_dword v[116:117], v140, off sc1
	global_store_dword v[118:119], v141, off sc1
	global_store_dword v[120:121], v142, off sc1
	global_store_dword v[122:123], v143, off sc1
	global_store_dword v[124:125], v144, off sc1
	global_store_dword v[126:127], v145, off sc1
	global_store_dword v[128:129], v146, off sc1
	global_store_dword v[48:49], v147, off sc1
	global_load_dword v115, v[132:133], off
	global_load_dword v62, v[70:71], off offset:256
	v_add_u32_e32 v32, v73, v130
	v_add_u32_e32 v34, v101, v130
	v_add_u32_e32 v36, v102, v130
	v_add_u32_e32 v38, v103, v130
	v_add_u32_e32 v40, v104, v130
	v_add_u32_e32 v42, v105, v130
	v_add_u32_e32 v44, v106, v130
	v_add_u32_e32 v46, v107, v130
	v_add_u32_e32 v48, v108, v130
	v_add_u32_e32 v50, v109, v130
	v_add_u32_e32 v52, v110, v130
	v_add_u32_e32 v54, v111, v130
	v_add_u32_e32 v56, v112, v130
	v_add_u32_e32 v58, v113, v130
	v_add_u32_e32 v60, v114, v130
	v_ashrrev_i32_e32 v33, 31, v32
	v_ashrrev_i32_e32 v35, 31, v34
	v_ashrrev_i32_e32 v37, 31, v36
	v_ashrrev_i32_e32 v39, 31, v38
	v_ashrrev_i32_e32 v41, 31, v40
	v_ashrrev_i32_e32 v43, 31, v42
	v_ashrrev_i32_e32 v45, 31, v44
	v_ashrrev_i32_e32 v47, 31, v46
	v_ashrrev_i32_e32 v49, 31, v48
	v_ashrrev_i32_e32 v51, 31, v50
	v_ashrrev_i32_e32 v53, 31, v52
	v_ashrrev_i32_e32 v55, 31, v54
	v_ashrrev_i32_e32 v57, 31, v56
	v_ashrrev_i32_e32 v59, 31, v58
	v_ashrrev_i32_e32 v61, 31, v60
	v_lshl_add_u64 v[32:33], v[32:33], 2, s[12:13]
	v_lshl_add_u64 v[34:35], v[34:35], 2, s[12:13]
	v_lshl_add_u64 v[36:37], v[36:37], 2, s[12:13]
	v_lshl_add_u64 v[38:39], v[38:39], 2, s[12:13]
	v_lshl_add_u64 v[40:41], v[40:41], 2, s[12:13]
	v_lshl_add_u64 v[42:43], v[42:43], 2, s[12:13]
	v_lshl_add_u64 v[44:45], v[44:45], 2, s[12:13]
	v_lshl_add_u64 v[46:47], v[46:47], 2, s[12:13]
	v_lshl_add_u64 v[48:49], v[48:49], 2, s[12:13]
	v_lshl_add_u64 v[50:51], v[50:51], 2, s[12:13]
	v_lshl_add_u64 v[52:53], v[52:53], 2, s[12:13]
	v_lshl_add_u64 v[54:55], v[54:55], 2, s[12:13]
	v_lshl_add_u64 v[56:57], v[56:57], 2, s[12:13]
	v_lshl_add_u64 v[58:59], v[58:59], 2, s[12:13]
	v_lshl_add_u64 v[60:61], v[60:61], 2, s[12:13]
	s_waitcnt vmcnt(0)
	v_fmac_f32_e32 v62, v16, v115
	global_store_dword v[70:71], v62, off offset:256 sc1
	global_load_dword v16, v[32:33], off
	global_load_dword v118, v[34:35], off
	global_load_dword v119, v[36:37], off
	global_load_dword v120, v[38:39], off
	global_load_dword v121, v[40:41], off
	global_load_dword v122, v[42:43], off
	global_load_dword v123, v[44:45], off
	global_load_dword v124, v[46:47], off
	global_load_dword v125, v[48:49], off
	global_load_dword v126, v[50:51], off
	global_load_dword v127, v[52:53], off
	global_load_dword v128, v[54:55], off
	global_load_dword v129, v[56:57], off
	global_load_dword v130, v[58:59], off
	global_load_dword v131, v[60:61], off
	v_or_b32_e32 v62, 0x60, v72
	v_ashrrev_i32_e32 v63, 31, v62
	v_lshl_add_u64 v[116:117], v[62:63], 2, s[52:53]
	s_waitcnt vmcnt(14)
	v_fmac_f32_e32 v16, v17, v115
	s_waitcnt vmcnt(13)
	v_fmac_f32_e32 v118, v18, v115
	s_waitcnt vmcnt(12)
	v_fmac_f32_e32 v119, v19, v115
	s_waitcnt vmcnt(11)
	v_fmac_f32_e32 v120, v20, v115
	s_waitcnt vmcnt(10)
	v_fmac_f32_e32 v121, v21, v115
	s_waitcnt vmcnt(9)
	v_fmac_f32_e32 v122, v22, v115
	s_waitcnt vmcnt(8)
	v_fmac_f32_e32 v123, v23, v115
	s_waitcnt vmcnt(7)
	v_fmac_f32_e32 v124, v24, v115
	s_waitcnt vmcnt(6)
	v_fmac_f32_e32 v125, v25, v115
	s_waitcnt vmcnt(5)
	v_fmac_f32_e32 v126, v26, v115
	s_waitcnt vmcnt(4)
	v_fmac_f32_e32 v127, v27, v115
	s_waitcnt vmcnt(3)
	v_fmac_f32_e32 v128, v28, v115
	s_waitcnt vmcnt(2)
	v_fmac_f32_e32 v129, v29, v115
	s_waitcnt vmcnt(1)
	v_fmac_f32_e32 v130, v30, v115
	s_waitcnt vmcnt(0)
	v_fmac_f32_e32 v131, v31, v115
	global_store_dword v[32:33], v16, off sc1
	global_store_dword v[34:35], v118, off sc1
	global_store_dword v[36:37], v119, off sc1
	global_store_dword v[38:39], v120, off sc1
	global_store_dword v[40:41], v121, off sc1
	global_store_dword v[42:43], v122, off sc1
	global_store_dword v[44:45], v123, off sc1
	global_store_dword v[46:47], v124, off sc1
	global_store_dword v[48:49], v125, off sc1
	global_store_dword v[50:51], v126, off sc1
	global_store_dword v[52:53], v127, off sc1
	global_store_dword v[54:55], v128, off sc1
	global_store_dword v[56:57], v129, off sc1
	global_store_dword v[58:59], v130, off sc1
	global_store_dword v[60:61], v131, off sc1
	global_load_dword v46, v[116:117], off
	global_load_dword v47, v[70:71], off offset:384
	v_add_u32_e32 v16, v73, v62
	v_add_u32_e32 v18, v101, v62
	v_add_u32_e32 v20, v102, v62
	v_add_u32_e32 v22, v103, v62
	v_add_u32_e32 v24, v104, v62
	v_add_u32_e32 v26, v105, v62
	v_add_u32_e32 v28, v106, v62
	v_add_u32_e32 v30, v107, v62
	v_add_u32_e32 v32, v108, v62
	v_add_u32_e32 v34, v109, v62
	v_add_u32_e32 v36, v110, v62
	v_add_u32_e32 v38, v111, v62
	v_add_u32_e32 v40, v112, v62
	v_add_u32_e32 v42, v113, v62
	v_add_u32_e32 v44, v114, v62
	v_ashrrev_i32_e32 v17, 31, v16
	v_ashrrev_i32_e32 v19, 31, v18
	v_ashrrev_i32_e32 v21, 31, v20
	v_ashrrev_i32_e32 v23, 31, v22
	v_ashrrev_i32_e32 v25, 31, v24
	v_ashrrev_i32_e32 v27, 31, v26
	v_ashrrev_i32_e32 v29, 31, v28
	v_ashrrev_i32_e32 v31, 31, v30
	v_ashrrev_i32_e32 v33, 31, v32
	v_ashrrev_i32_e32 v35, 31, v34
	v_ashrrev_i32_e32 v37, 31, v36
	v_ashrrev_i32_e32 v39, 31, v38
	v_ashrrev_i32_e32 v41, 31, v40
	v_ashrrev_i32_e32 v43, 31, v42
	v_ashrrev_i32_e32 v45, 31, v44
	v_lshl_add_u64 v[16:17], v[16:17], 2, s[12:13]
	v_lshl_add_u64 v[18:19], v[18:19], 2, s[12:13]
	v_lshl_add_u64 v[20:21], v[20:21], 2, s[12:13]
	v_lshl_add_u64 v[22:23], v[22:23], 2, s[12:13]
	v_lshl_add_u64 v[24:25], v[24:25], 2, s[12:13]
	v_lshl_add_u64 v[26:27], v[26:27], 2, s[12:13]
	v_lshl_add_u64 v[28:29], v[28:29], 2, s[12:13]
	v_lshl_add_u64 v[30:31], v[30:31], 2, s[12:13]
	v_lshl_add_u64 v[32:33], v[32:33], 2, s[12:13]
	v_lshl_add_u64 v[34:35], v[34:35], 2, s[12:13]
	v_lshl_add_u64 v[36:37], v[36:37], 2, s[12:13]
	v_lshl_add_u64 v[38:39], v[38:39], 2, s[12:13]
	v_lshl_add_u64 v[40:41], v[40:41], 2, s[12:13]
	v_lshl_add_u64 v[42:43], v[42:43], 2, s[12:13]
	v_lshl_add_u64 v[44:45], v[44:45], 2, s[12:13]
	s_waitcnt vmcnt(0)
	v_fmac_f32_e32 v47, v0, v46
	global_store_dword v[70:71], v47, off offset:384 sc1
	global_load_dword v0, v[16:17], off
	s_nop 0
	global_load_dword v47, v[18:19], off
	global_load_dword v48, v[20:21], off
	global_load_dword v49, v[22:23], off
	global_load_dword v50, v[24:25], off
	global_load_dword v51, v[26:27], off
	global_load_dword v52, v[28:29], off
	global_load_dword v53, v[30:31], off
	global_load_dword v54, v[32:33], off
	global_load_dword v55, v[34:35], off
	global_load_dword v56, v[36:37], off
	global_load_dword v57, v[38:39], off
	global_load_dword v58, v[40:41], off
	global_load_dword v59, v[42:43], off
	global_load_dword v60, v[44:45], off
	s_waitcnt vmcnt(14)
	v_fmac_f32_e32 v0, v1, v46
	s_waitcnt vmcnt(13)
	v_fmac_f32_e32 v47, v2, v46
	s_waitcnt vmcnt(12)
	v_fmac_f32_e32 v48, v3, v46
	s_waitcnt vmcnt(11)
	v_fmac_f32_e32 v49, v4, v46
	s_waitcnt vmcnt(10)
	v_fmac_f32_e32 v50, v5, v46
	s_waitcnt vmcnt(9)
	v_fmac_f32_e32 v51, v6, v46
	s_waitcnt vmcnt(8)
	v_fmac_f32_e32 v52, v7, v46
	s_waitcnt vmcnt(7)
	v_fmac_f32_e32 v53, v8, v46
	s_waitcnt vmcnt(6)
	v_fmac_f32_e32 v54, v9, v46
	s_waitcnt vmcnt(5)
	v_fmac_f32_e32 v55, v10, v46
	s_waitcnt vmcnt(4)
	v_fmac_f32_e32 v56, v11, v46
	s_waitcnt vmcnt(3)
	v_fmac_f32_e32 v57, v12, v46
	s_waitcnt vmcnt(2)
	v_fmac_f32_e32 v58, v13, v46
	s_waitcnt vmcnt(1)
	v_fmac_f32_e32 v59, v14, v46
	s_waitcnt vmcnt(0)
	v_fmac_f32_e32 v60, v15, v46
	global_store_dword v[16:17], v0, off sc1
	global_store_dword v[18:19], v47, off sc1
	global_store_dword v[20:21], v48, off sc1
	global_store_dword v[22:23], v49, off sc1
	global_store_dword v[24:25], v50, off sc1
	global_store_dword v[26:27], v51, off sc1
	global_store_dword v[28:29], v52, off sc1
	global_store_dword v[30:31], v53, off sc1
	global_store_dword v[32:33], v54, off sc1
	global_store_dword v[34:35], v55, off sc1
	global_store_dword v[36:37], v56, off sc1
	global_store_dword v[38:39], v57, off sc1
	global_store_dword v[40:41], v58, off sc1
	global_store_dword v[42:43], v59, off sc1
	global_store_dword v[44:45], v60, off sc1
	s_cbranch_scc1 .LBB0_1641
.LBB0_1637:
	s_ashr_i32 s2, s10, 31
	s_lshr_b32 s2, s2, 26
	s_add_i32 s2, s10, s2
	s_ashr_i32 s11, s2, 6
	s_andn2_b32 s2, s2, 63
	s_sub_i32 s2, s10, s2
	s_ashr_i32 s16, s2, 31
	s_lshr_b32 s16, s16, 29
	s_add_i32 s16, s2, s16
	s_and_b32 s52, s16, -8
	s_lshl_b32 s11, s11, 3
	s_sub_i32 s2, s2, s52
	s_add_i32 s2, s2, s11
	s_lshl_b32 s16, s16, 4
	s_lshl_b32 s11, s2, 7
	s_and_b32 s16, s16, 0xffffff80
	s_cmp_eq_u32 s39, 1
	s_cbranch_scc1 .Lgk_pfhead_p26
	s_mul_i32 s38, s2, 0xb0000
	s_add_u32 s18, s14, s38
	s_addc_u32 s19, s15, 0
	s_add_u32 s18, s18, 0x879f000
	s_addc_u32 s19, s19, 0
	s_add_u32 s20, s18, 0x2c000
	s_addc_u32 s21, s19, 0
	s_add_u32 s22, s20, 0x2c000
	s_addc_u32 s23, s21, 0
	s_add_u32 s24, s22, 0x2c000
	s_addc_u32 s25, s23, 0
	s_mul_i32 s38, s16, 0x1600
	s_add_u32 s26, s14, s38
	s_addc_u32 s27, s15, 0
	s_add_u32 s26, s26, 0x5620000
	s_addc_u32 s27, s27, 0
	s_add_u32 s28, s26, 0x2c000
	s_addc_u32 s29, s27, 0
	s_add_u32 s30, s28, 0x2c000
	s_addc_u32 s31, s29, 0
	s_add_u32 s34, s30, 0x2c000
	s_addc_u32 s35, s31, 0
	v_readfirstlane_b32 s36, v77
	v_mov_b32_e32 v254, v64
	s_mov_b32 m0, s36
	s_nop 0
	global_load_lds_dwordx4 v254, s[18:19]
	s_add_u32 m0, m0, 0x1000
	s_nop 0
	global_load_lds_dwordx4 v254, s[20:21]
	s_add_u32 m0, m0, 0x1000
	s_nop 0
	global_load_lds_dwordx4 v254, s[22:23]
	s_add_u32 m0, m0, 0x1000
	s_nop 0
	global_load_lds_dwordx4 v254, s[24:25]
	s_add_u32 m0, m0, 0x1000
	s_nop 0
	global_load_lds_dwordx4 v254, s[26:27]
	s_add_u32 m0, m0, 0x1000
	s_nop 0
	global_load_lds_dwordx4 v254, s[28:29]
	s_add_u32 m0, m0, 0x1000
	s_nop 0
	global_load_lds_dwordx4 v254, s[30:31]
	s_add_u32 m0, m0, 0x1000
	s_nop 0
	global_load_lds_dwordx4 v254, s[34:35]
	v_add_u32_e32 v254, 0x80, v254
	s_add_u32 m0, s36, 0x8000
	s_nop 0
	global_load_lds_dwordx4 v254, s[18:19]
	s_add_u32 m0, m0, 0x1000
	s_nop 0
	global_load_lds_dwordx4 v254, s[20:21]
	s_add_u32 m0, m0, 0x1000
	s_nop 0
	global_load_lds_dwordx4 v254, s[22:23]
	s_add_u32 m0, m0, 0x1000
	s_nop 0
	global_load_lds_dwordx4 v254, s[24:25]
	s_add_u32 m0, m0, 0x1000
	s_nop 0
	global_load_lds_dwordx4 v254, s[26:27]
	s_add_u32 m0, m0, 0x1000
	s_nop 0
	global_load_lds_dwordx4 v254, s[28:29]
	s_add_u32 m0, m0, 0x1000
	s_nop 0
	global_load_lds_dwordx4 v254, s[30:31]
	s_add_u32 m0, m0, 0x1000
	s_nop 0
	global_load_lds_dwordx4 v254, s[34:35]
	v_add_u32_e32 v254, 0x80, v254

.Lgk_loop_p26:
	s_waitcnt vmcnt(8)
	s_barrier
	ds_read_b128 v[70:73], v93
	ds_read_b128 v[102:105], v94 offset:16384
	ds_read_b128 v[106:109], v94 offset:20480
	ds_read_b128 v[110:113], v94 offset:24576
	ds_read_b128 v[114:117], v94 offset:28672
	ds_read_b128 v[118:121], v95
	ds_read_b128 v[122:125], v96 offset:16384
	ds_read_b128 v[126:129], v96 offset:20480
	ds_read_b128 v[130:133], v96 offset:24576
	ds_read_b128 v[134:137], v96 offset:28672
	ds_read_b128 v[138:141], v97
	ds_read_b128 v[162:165], v98 offset:16384
	ds_read_b128 v[166:169], v98 offset:20480
	ds_read_b128 v[170:173], v98 offset:24576
	ds_read_b128 v[174:177], v98 offset:28672
	ds_read_b128 v[178:181], v99
	ds_read_b128 v[182:185], v100 offset:16384
	ds_read_b128 v[186:189], v100 offset:20480
	ds_read_b128 v[190:193], v100 offset:24576
	ds_read_b128 v[194:197], v100 offset:28672
	s_waitcnt lgkmcnt(0)
	s_barrier
	s_mov_b32 m0, s36
	s_setprio 1
	v_mfma_f32_32x32x16_bf16 v[48:63], v[70:73], v[102:105], v[48:63]
	v_mfma_f32_32x32x16_bf16 v[32:47], v[70:73], v[106:109], v[32:47]
	global_load_lds_dwordx4 v254, s[18:19]
	s_add_u32 m0, m0, 0x1000
	v_mfma_f32_32x32x16_bf16 v[16:31], v[70:73], v[110:113], v[16:31]
	v_mfma_f32_32x32x16_bf16 v[0:15], v[70:73], v[114:117], v[0:15]
	global_load_lds_dwordx4 v254, s[20:21]
	s_add_u32 m0, m0, 0x1000
	v_mfma_f32_32x32x16_bf16 v[48:63], v[118:121], v[122:125], v[48:63]
	v_mfma_f32_32x32x16_bf16 v[32:47], v[118:121], v[126:129], v[32:47]
	global_load_lds_dwordx4 v254, s[22:23]
	s_add_u32 m0, m0, 0x1000
	v_mfma_f32_32x32x16_bf16 v[16:31], v[118:121], v[130:133], v[16:31]
	v_mfma_f32_32x32x16_bf16 v[0:15], v[118:121], v[134:137], v[0:15]
	global_load_lds_dwordx4 v254, s[24:25]
	s_add_u32 m0, m0, 0x1000
	v_mfma_f32_32x32x16_bf16 v[48:63], v[138:141], v[162:165], v[48:63]
	v_mfma_f32_32x32x16_bf16 v[32:47], v[138:141], v[166:169], v[32:47]
	global_load_lds_dwordx4 v254, s[26:27]
	s_add_u32 m0, m0, 0x1000
	v_mfma_f32_32x32x16_bf16 v[16:31], v[138:141], v[170:173], v[16:31]
	v_mfma_f32_32x32x16_bf16 v[0:15], v[138:141], v[174:177], v[0:15]
	global_load_lds_dwordx4 v254, s[28:29]
	s_add_u32 m0, m0, 0x1000
	v_mfma_f32_32x32x16_bf16 v[48:63], v[178:181], v[182:185], v[48:63]
	v_mfma_f32_32x32x16_bf16 v[32:47], v[178:181], v[186:189], v[32:47]
	global_load_lds_dwordx4 v254, s[30:31]
	s_add_u32 m0, m0, 0x1000
	v_mfma_f32_32x32x16_bf16 v[16:31], v[178:181], v[190:193], v[16:31]
	v_mfma_f32_32x32x16_bf16 v[0:15], v[178:181], v[194:197], v[0:15]
	global_load_lds_dwordx4 v254, s[34:35]
	s_setprio 0
	v_add_u32_e32 v254, 0x80, v254
	s_waitcnt vmcnt(8)
	s_barrier
	ds_read_b128 v[70:73], v93 offset:32768
	ds_read_b128 v[102:105], v94 offset:49152
	ds_read_b128 v[106:109], v94 offset:53248
	ds_read_b128 v[110:113], v94 offset:57344
	ds_read_b128 v[114:117], v94 offset:61440
	ds_read_b128 v[118:121], v95 offset:32768
	ds_read_b128 v[122:125], v96 offset:49152
	ds_read_b128 v[126:129], v96 offset:53248
	ds_read_b128 v[130:133], v96 offset:57344
	ds_read_b128 v[134:137], v96 offset:61440
	ds_read_b128 v[138:141], v97 offset:32768
	ds_read_b128 v[162:165], v98 offset:49152
	ds_read_b128 v[166:169], v98 offset:53248
	ds_read_b128 v[170:173], v98 offset:57344
	ds_read_b128 v[174:177], v98 offset:61440
	ds_read_b128 v[178:181], v99 offset:32768
	ds_read_b128 v[182:185], v100 offset:49152
	ds_read_b128 v[186:189], v100 offset:53248
	ds_read_b128 v[190:193], v100 offset:57344
	ds_read_b128 v[194:197], v100 offset:61440
	s_waitcnt lgkmcnt(0)
	s_barrier
	s_add_u32 m0, s36, 0x8000
	s_setprio 1
	v_mfma_f32_32x32x16_bf16 v[48:63], v[70:73], v[102:105], v[48:63]
	v_mfma_f32_32x32x16_bf16 v[32:47], v[70:73], v[106:109], v[32:47]
	global_load_lds_dwordx4 v254, s[18:19]
	s_add_u32 m0, m0, 0x1000
	v_mfma_f32_32x32x16_bf16 v[16:31], v[70:73], v[110:113], v[16:31]
	v_mfma_f32_32x32x16_bf16 v[0:15], v[70:73], v[114:117], v[0:15]
	global_load_lds_dwordx4 v254, s[20:21]
	s_add_u32 m0, m0, 0x1000
	v_mfma_f32_32x32x16_bf16 v[48:63], v[118:121], v[122:125], v[48:63]
	v_mfma_f32_32x32x16_bf16 v[32:47], v[118:121], v[126:129], v[32:47]
	global_load_lds_dwordx4 v254, s[22:23]
	s_add_u32 m0, m0, 0x1000
	v_mfma_f32_32x32x16_bf16 v[16:31], v[118:121], v[130:133], v[16:31]
	v_mfma_f32_32x32x16_bf16 v[0:15], v[118:121], v[134:137], v[0:15]
	global_load_lds_dwordx4 v254, s[24:25]
	s_add_u32 m0, m0, 0x1000
	v_mfma_f32_32x32x16_bf16 v[48:63], v[138:141], v[162:165], v[48:63]
	v_mfma_f32_32x32x16_bf16 v[32:47], v[138:141], v[166:169], v[32:47]
	global_load_lds_dwordx4 v254, s[26:27]
	s_add_u32 m0, m0, 0x1000
	v_mfma_f32_32x32x16_bf16 v[16:31], v[138:141], v[170:173], v[16:31]
	v_mfma_f32_32x32x16_bf16 v[0:15], v[138:141], v[174:177], v[0:15]
	global_load_lds_dwordx4 v254, s[28:29]
	s_add_u32 m0, m0, 0x1000
	v_mfma_f32_32x32x16_bf16 v[48:63], v[178:181], v[182:185], v[48:63]
	v_mfma_f32_32x32x16_bf16 v[32:47], v[178:181], v[186:189], v[32:47]
	global_load_lds_dwordx4 v254, s[30:31]
	s_add_u32 m0, m0, 0x1000
	v_mfma_f32_32x32x16_bf16 v[16:31], v[178:181], v[190:193], v[16:31]
	v_mfma_f32_32x32x16_bf16 v[0:15], v[178:181], v[194:197], v[0:15]
	global_load_lds_dwordx4 v254, s[34:35]
	s_setprio 0
	v_add_u32_e32 v254, 0x80, v254
	s_sub_u32 s37, s37, 1
	s_cmp_lg_u32 s37, 0
	s_cbranch_scc1 .Lgk_loop_p26
	s_add_u32 s40, s10, s33
	s_cmp_gt_u32 s40, 0x3ff
	s_cbranch_scc1 .Lgk_tailplain_p26
.LBB0_1637_pf_p26:
	s_ashr_i32 s41, s40, 31
	s_lshr_b32 s41, s41, 26
	s_add_i32 s41, s40, s41
	s_ashr_i32 s42, s41, 6
	s_andn2_b32 s41, s41, 63
	s_sub_i32 s41, s40, s41
	s_ashr_i32 s43, s41, 31
	s_lshr_b32 s43, s43, 29
	s_add_i32 s43, s41, s43
	s_and_b32 s44, s43, -8
	s_lshl_b32 s42, s42, 3
	s_sub_i32 s41, s41, s44
	s_add_i32 s41, s41, s42
	s_lshl_b32 s43, s43, 4
	s_lshl_b32 s42, s41, 7
	s_and_b32 s43, s43, 0xffffff80
	s_mul_i32 s38, s41, 0xb0000
	s_add_u32 s18, s14, s38
	s_addc_u32 s19, s15, 0
	s_add_u32 s18, s18, 0x879f000
	s_addc_u32 s19, s19, 0
	s_add_u32 s20, s18, 0x2c000
	s_addc_u32 s21, s19, 0
	s_add_u32 s22, s20, 0x2c000
	s_addc_u32 s23, s21, 0
	s_add_u32 s24, s22, 0x2c000
	s_addc_u32 s25, s23, 0
	s_mul_i32 s38, s43, 0x1600
	s_add_u32 s26, s14, s38
	s_addc_u32 s27, s15, 0
	s_add_u32 s26, s26, 0x5620000
	s_addc_u32 s27, s27, 0
	s_add_u32 s28, s26, 0x2c000
	s_addc_u32 s29, s27, 0
	s_add_u32 s30, s28, 0x2c000
	s_addc_u32 s31, s29, 0
	s_add_u32 s34, s30, 0x2c000
	s_addc_u32 s35, s31, 0
	v_mov_b32_e32 v254, v64
	s_mov_b32 s39, 1
	s_waitcnt vmcnt(8)
	s_barrier
	ds_read_b128 v[70:73], v93
	ds_read_b128 v[102:105], v94 offset:16384
	ds_read_b128 v[106:109], v94 offset:20480
	ds_read_b128 v[110:113], v94 offset:24576
	ds_read_b128 v[114:117], v94 offset:28672
	ds_read_b128 v[118:121], v95
	ds_read_b128 v[122:125], v96 offset:16384
	ds_read_b128 v[126:129], v96 offset:20480
	ds_read_b128 v[130:133], v96 offset:24576
	ds_read_b128 v[134:137], v96 offset:28672
	ds_read_b128 v[138:141], v97
	ds_read_b128 v[162:165], v98 offset:16384
	ds_read_b128 v[166:169], v98 offset:20480
	ds_read_b128 v[170:173], v98 offset:24576
	ds_read_b128 v[174:177], v98 offset:28672
	ds_read_b128 v[178:181], v99
	ds_read_b128 v[182:185], v100 offset:16384
	ds_read_b128 v[186:189], v100 offset:20480
	ds_read_b128 v[190:193], v100 offset:24576
	ds_read_b128 v[194:197], v100 offset:28672
	s_waitcnt lgkmcnt(0)
	s_barrier
	s_mov_b32 m0, s36
	s_setprio 1
	v_mfma_f32_32x32x16_bf16 v[48:63], v[70:73], v[102:105], v[48:63]
	v_mfma_f32_32x32x16_bf16 v[32:47], v[70:73], v[106:109], v[32:47]
	global_load_lds_dwordx4 v254, s[18:19]
	s_add_u32 m0, m0, 0x1000
	v_mfma_f32_32x32x16_bf16 v[16:31], v[70:73], v[110:113], v[16:31]
	v_mfma_f32_32x32x16_bf16 v[0:15], v[70:73], v[114:117], v[0:15]
	global_load_lds_dwordx4 v254, s[20:21]
	s_add_u32 m0, m0, 0x1000
	v_mfma_f32_32x32x16_bf16 v[48:63], v[118:121], v[122:125], v[48:63]
	v_mfma_f32_32x32x16_bf16 v[32:47], v[118:121], v[126:129], v[32:47]
	global_load_lds_dwordx4 v254, s[22:23]
	s_add_u32 m0, m0, 0x1000
	v_mfma_f32_32x32x16_bf16 v[16:31], v[118:121], v[130:133], v[16:31]
	v_mfma_f32_32x32x16_bf16 v[0:15], v[118:121], v[134:137], v[0:15]
	global_load_lds_dwordx4 v254, s[24:25]
	s_add_u32 m0, m0, 0x1000
	v_mfma_f32_32x32x16_bf16 v[48:63], v[138:141], v[162:165], v[48:63]
	v_mfma_f32_32x32x16_bf16 v[32:47], v[138:141], v[166:169], v[32:47]
	global_load_lds_dwordx4 v254, s[26:27]
	s_add_u32 m0, m0, 0x1000
	v_mfma_f32_32x32x16_bf16 v[16:31], v[138:141], v[170:173], v[16:31]
	v_mfma_f32_32x32x16_bf16 v[0:15], v[138:141], v[174:177], v[0:15]
	global_load_lds_dwordx4 v254, s[28:29]
	s_add_u32 m0, m0, 0x1000
	v_mfma_f32_32x32x16_bf16 v[48:63], v[178:181], v[182:185], v[48:63]
	v_mfma_f32_32x32x16_bf16 v[32:47], v[178:181], v[186:189], v[32:47]
	global_load_lds_dwordx4 v254, s[30:31]
	s_add_u32 m0, m0, 0x1000
	v_mfma_f32_32x32x16_bf16 v[16:31], v[178:181], v[190:193], v[16:31]
	v_mfma_f32_32x32x16_bf16 v[0:15], v[178:181], v[194:197], v[0:15]
	global_load_lds_dwordx4 v254, s[34:35]
	s_setprio 0
	v_add_u32_e32 v254, 0x80, v254
	s_waitcnt vmcnt(8)
	s_barrier
	ds_read_b128 v[70:73], v93 offset:32768
	ds_read_b128 v[102:105], v94 offset:49152
	ds_read_b128 v[106:109], v94 offset:53248
	ds_read_b128 v[110:113], v94 offset:57344
	ds_read_b128 v[114:117], v94 offset:61440
	ds_read_b128 v[118:121], v95 offset:32768
	ds_read_b128 v[122:125], v96 offset:49152
	ds_read_b128 v[126:129], v96 offset:53248
	ds_read_b128 v[130:133], v96 offset:57344
	ds_read_b128 v[134:137], v96 offset:61440
	ds_read_b128 v[138:141], v97 offset:32768
	ds_read_b128 v[162:165], v98 offset:49152
	ds_read_b128 v[166:169], v98 offset:53248
	ds_read_b128 v[170:173], v98 offset:57344
	ds_read_b128 v[174:177], v98 offset:61440
	ds_read_b128 v[178:181], v99 offset:32768
	ds_read_b128 v[182:185], v100 offset:49152
	ds_read_b128 v[186:189], v100 offset:53248
	ds_read_b128 v[190:193], v100 offset:57344
	ds_read_b128 v[194:197], v100 offset:61440
	s_waitcnt lgkmcnt(0)
	s_barrier
	s_add_u32 m0, s36, 0x8000
	s_setprio 1
	v_mfma_f32_32x32x16_bf16 v[48:63], v[70:73], v[102:105], v[48:63]
	v_mfma_f32_32x32x16_bf16 v[32:47], v[70:73], v[106:109], v[32:47]
	global_load_lds_dwordx4 v254, s[18:19]
	s_add_u32 m0, m0, 0x1000
	v_mfma_f32_32x32x16_bf16 v[16:31], v[70:73], v[110:113], v[16:31]
	v_mfma_f32_32x32x16_bf16 v[0:15], v[70:73], v[114:117], v[0:15]
	global_load_lds_dwordx4 v254, s[20:21]
	s_add_u32 m0, m0, 0x1000
	v_mfma_f32_32x32x16_bf16 v[48:63], v[118:121], v[122:125], v[48:63]
	v_mfma_f32_32x32x16_bf16 v[32:47], v[118:121], v[126:129], v[32:47]
	global_load_lds_dwordx4 v254, s[22:23]
	s_add_u32 m0, m0, 0x1000
	v_mfma_f32_32x32x16_bf16 v[16:31], v[118:121], v[130:133], v[16:31]
	v_mfma_f32_32x32x16_bf16 v[0:15], v[118:121], v[134:137], v[0:15]
	global_load_lds_dwordx4 v254, s[24:25]
	s_add_u32 m0, m0, 0x1000
	v_mfma_f32_32x32x16_bf16 v[48:63], v[138:141], v[162:165], v[48:63]
	v_mfma_f32_32x32x16_bf16 v[32:47], v[138:141], v[166:169], v[32:47]
	global_load_lds_dwordx4 v254, s[26:27]
	s_add_u32 m0, m0, 0x1000
	v_mfma_f32_32x32x16_bf16 v[16:31], v[138:141], v[170:173], v[16:31]
	v_mfma_f32_32x32x16_bf16 v[0:15], v[138:141], v[174:177], v[0:15]
	global_load_lds_dwordx4 v254, s[28:29]
	s_add_u32 m0, m0, 0x1000
	v_mfma_f32_32x32x16_bf16 v[48:63], v[178:181], v[182:185], v[48:63]
	v_mfma_f32_32x32x16_bf16 v[32:47], v[178:181], v[186:189], v[32:47]
	global_load_lds_dwordx4 v254, s[30:31]
	s_add_u32 m0, m0, 0x1000
	v_mfma_f32_32x32x16_bf16 v[16:31], v[178:181], v[190:193], v[16:31]
	v_mfma_f32_32x32x16_bf16 v[0:15], v[178:181], v[194:197], v[0:15]
	global_load_lds_dwordx4 v254, s[34:35]
	s_setprio 0
	v_add_u32_e32 v254, 0x80, v254
	s_branch .LBB0_1636
.Lgk_tailplain_p26:
	s_mov_b32 s39, 0
	s_waitcnt vmcnt(8)
	s_barrier
	ds_read_b128 v[70:73], v93
	ds_read_b128 v[102:105], v94 offset:16384
	ds_read_b128 v[106:109], v94 offset:20480
	ds_read_b128 v[110:113], v94 offset:24576
	ds_read_b128 v[114:117], v94 offset:28672
	ds_read_b128 v[118:121], v95
	ds_read_b128 v[122:125], v96 offset:16384
	ds_read_b128 v[126:129], v96 offset:20480
	ds_read_b128 v[130:133], v96 offset:24576
	ds_read_b128 v[134:137], v96 offset:28672
	ds_read_b128 v[138:141], v97
	ds_read_b128 v[162:165], v98 offset:16384
	ds_read_b128 v[166:169], v98 offset:20480
	ds_read_b128 v[170:173], v98 offset:24576
	ds_read_b128 v[174:177], v98 offset:28672
	ds_read_b128 v[178:181], v99
	ds_read_b128 v[182:185], v100 offset:16384
	ds_read_b128 v[186:189], v100 offset:20480
	ds_read_b128 v[190:193], v100 offset:24576
	ds_read_b128 v[194:197], v100 offset:28672
	s_waitcnt lgkmcnt(0)
	s_barrier
	s_setprio 1
	v_mfma_f32_32x32x16_bf16 v[48:63], v[70:73], v[102:105], v[48:63]
	v_mfma_f32_32x32x16_bf16 v[32:47], v[70:73], v[106:109], v[32:47]
	v_mfma_f32_32x32x16_bf16 v[16:31], v[70:73], v[110:113], v[16:31]
	v_mfma_f32_32x32x16_bf16 v[0:15], v[70:73], v[114:117], v[0:15]
	v_mfma_f32_32x32x16_bf16 v[48:63], v[118:121], v[122:125], v[48:63]
	v_mfma_f32_32x32x16_bf16 v[32:47], v[118:121], v[126:129], v[32:47]
	v_mfma_f32_32x32x16_bf16 v[16:31], v[118:121], v[130:133], v[16:31]
	v_mfma_f32_32x32x16_bf16 v[0:15], v[118:121], v[134:137], v[0:15]
	v_mfma_f32_32x32x16_bf16 v[48:63], v[138:141], v[162:165], v[48:63]
	v_mfma_f32_32x32x16_bf16 v[32:47], v[138:141], v[166:169], v[32:47]
	v_mfma_f32_32x32x16_bf16 v[16:31], v[138:141], v[170:173], v[16:31]
	v_mfma_f32_32x32x16_bf16 v[0:15], v[138:141], v[174:177], v[0:15]
	v_mfma_f32_32x32x16_bf16 v[48:63], v[178:181], v[182:185], v[48:63]
	v_mfma_f32_32x32x16_bf16 v[32:47], v[178:181], v[186:189], v[32:47]
	v_mfma_f32_32x32x16_bf16 v[16:31], v[178:181], v[190:193], v[16:31]
	v_mfma_f32_32x32x16_bf16 v[0:15], v[178:181], v[194:197], v[0:15]
	s_setprio 0
	s_waitcnt vmcnt(0)
	s_barrier
	ds_read_b128 v[70:73], v93 offset:32768
	ds_read_b128 v[102:105], v94 offset:49152
	ds_read_b128 v[106:109], v94 offset:53248
	ds_read_b128 v[110:113], v94 offset:57344
	ds_read_b128 v[114:117], v94 offset:61440
	ds_read_b128 v[118:121], v95 offset:32768
	ds_read_b128 v[122:125], v96 offset:49152
	ds_read_b128 v[126:129], v96 offset:53248
	ds_read_b128 v[130:133], v96 offset:57344
	ds_read_b128 v[134:137], v96 offset:61440
	ds_read_b128 v[138:141], v97 offset:32768
	ds_read_b128 v[162:165], v98 offset:49152
	ds_read_b128 v[166:169], v98 offset:53248
	ds_read_b128 v[170:173], v98 offset:57344
	ds_read_b128 v[174:177], v98 offset:61440
	ds_read_b128 v[178:181], v99 offset:32768
	ds_read_b128 v[182:185], v100 offset:49152
	ds_read_b128 v[186:189], v100 offset:53248
	ds_read_b128 v[190:193], v100 offset:57344
	ds_read_b128 v[194:197], v100 offset:61440
	s_waitcnt lgkmcnt(0)
	s_barrier
	s_setprio 1
	v_mfma_f32_32x32x16_bf16 v[48:63], v[70:73], v[102:105], v[48:63]
	v_mfma_f32_32x32x16_bf16 v[32:47], v[70:73], v[106:109], v[32:47]
	v_mfma_f32_32x32x16_bf16 v[16:31], v[70:73], v[110:113], v[16:31]
	v_mfma_f32_32x32x16_bf16 v[0:15], v[70:73], v[114:117], v[0:15]
	v_mfma_f32_32x32x16_bf16 v[48:63], v[118:121], v[122:125], v[48:63]
	v_mfma_f32_32x32x16_bf16 v[32:47], v[118:121], v[126:129], v[32:47]
	v_mfma_f32_32x32x16_bf16 v[16:31], v[118:121], v[130:133], v[16:31]
	v_mfma_f32_32x32x16_bf16 v[0:15], v[118:121], v[134:137], v[0:15]
	v_mfma_f32_32x32x16_bf16 v[48:63], v[138:141], v[162:165], v[48:63]
	v_mfma_f32_32x32x16_bf16 v[32:47], v[138:141], v[166:169], v[32:47]
	v_mfma_f32_32x32x16_bf16 v[16:31], v[138:141], v[170:173], v[16:31]
	v_mfma_f32_32x32x16_bf16 v[0:15], v[138:141], v[174:177], v[0:15]
	v_mfma_f32_32x32x16_bf16 v[48:63], v[178:181], v[182:185], v[48:63]
	v_mfma_f32_32x32x16_bf16 v[32:47], v[178:181], v[186:189], v[32:47]
	v_mfma_f32_32x32x16_bf16 v[16:31], v[178:181], v[190:193], v[16:31]
	v_mfma_f32_32x32x16_bf16 v[0:15], v[178:181], v[194:197], v[0:15]
	s_setprio 0
	s_branch .LBB0_1636
